# v19: v16 + instruction selection: every packed fp32 VALU op (v_pk_mul/add/fma_f32) after the prologue split into its two scalar ops (bit-identical)
# baseline (speedup 1.0000x reference)
; #define GAS __attribute__((address_space(1)))
; __device__ __forceinline__ unsigned pk2(float lo, float hi) { const f32x2_t v = {lo, hi}; const bf16x2_t b = __builtin_convertvector(v, bf16x2_t); return __builtin_bit_cast(unsigned, b); }
; __device__ __forceinline__ void norm_mod_phase(const Args& a, Frame& F, const float* gain, const float* modl, int sh_off, int sc_off, int nrows, const float* slab_gate) {
;     ...
; #pragma unroll
;         for (int j = 0; j < 8; ++j) ss += (v[j][0] * v[j][0] + v[j][1] * v[j][1]) + (v[j][2] * v[j][2] + v[j][3] * v[j][3]);
;         const float rstd = 1.0f / sqrtf(wave_sum(ss) * (1.0f / D) + EPS);
;         const float* mb = modl + (size_t)b * MOD_LD;
;         GAS v2u* o8 = (GAS v2u*)(HN + (size_t)r * D) + F.lane;
; #pragma unroll
;         for (int j = 0; j < 8; ++j) { const int c = 256 * j + 4 * F.lane;
;             const f32x4 g = *(const GAS f32x4*)(gain + c), sh = *(const GAS f32x4*)(mb + sh_off + c), sc = *(const GAS f32x4*)(mb + sc_off + c);
;             const f32x4 y = (v[j] * rstd) * g * (sc + 1.0f) + sh;
;             v2u w; w.x = pk2(y[0], y[1]); w.y = pk2(y[2], y[3]); o8[64 * j] = w; }
.LBB0_211:
	v_mul_f32_e32 v70, v66, v66
	v_mul_f32_e32 v71, v67, v67
	v_mul_f32_e32 v72, v62, v62
	v_mul_f32_e32 v73, v63, v63
	v_mul_f32_e32 v10, v68, v68
	v_mul_f32_e32 v11, v69, v69
	v_mul_f32_e32 v12, v64, v64
	v_mul_f32_e32 v13, v65, v65
	v_mov_b32_e32 v76, v70
	v_mov_b32_e32 v77, v72
	v_mov_b32_e32 v72, v71
	v_mul_f32_e32 v6, v60, v60
	v_mul_f32_e32 v7, v61, v61
	v_mul_f32_e32 v8, v58, v58
	v_mul_f32_e32 v9, v59, v59
	v_add_f32_e32 v70, v76, v72
	v_add_f32_e32 v71, v77, v73
	v_mov_b32_e32 v72, v10
	v_mov_b32_e32 v73, v12
	v_mov_b32_e32 v12, v11
	v_add_f32_e32 v10, v72, v12
	v_add_f32_e32 v11, v73, v13
	v_pk_mov_b32 v[12:13], v[8:9], v[6:7] op_sel:[1,0]
	v_mov_b32_e32 v9, v7
	v_add_f32_e32 v6, v12, v8
	v_add_f32_e32 v7, v13, v9
	v_add_f32_e32 v10, v70, v10
	v_add_f32_e32 v11, v71, v11
	v_add_f32_e32 v7, v6, v7
	v_add_f32_e32 v6, v6, v6
	v_mul_f32_e32 v6, v54, v54
	v_fma_f32 v8, v54, v54, v6
	v_fma_f32 v9, v55, v55, v6
	v_mul_f32_e32 v6, v56, v56
	v_add_f32_e32 v11, v10, v11
	v_add_f32_e32 v10, v10, v10
	v_fma_f32 v12, v56, v56, v6
	v_fma_f32 v13, v57, v57, v6
	v_mul_f32_e32 v8, v50, v50
	v_mul_f32_e32 v12, v51, v51
	v_mul_f32_e32 v6, v52, v52
	v_mul_f32_e32 v10, v53, v53
	v_mul_f32_e32 v2, v48, v48
	v_mul_f32_e32 v3, v49, v49
	v_mul_f32_e32 v4, v46, v46
	v_mul_f32_e32 v5, v47, v47
	v_add_f32_e32 v8, v8, v12
	v_add_f32_e32 v9, v9, v13
	v_add_f32_e32 v6, v6, v10
	v_add_f32_e32 v7, v7, v11
	s_min_i32 s6, s10, 0x4000
	v_add_f32_e32 v6, v8, v6
	v_add_f32_e32 v7, v9, v7
	v_pk_mov_b32 v[8:9], v[4:5], v[2:3] op_sel:[1,0]
	v_mov_b32_e32 v5, v3
	v_add_f32_e32 v2, v8, v4
	v_add_f32_e32 v3, v9, v5
	v_add_f32_e32 v7, v6, v7
	v_add_f32_e32 v6, v6, v6
	v_add_f32_e32 v3, v2, v3
	v_add_f32_e32 v2, v2, v2
	v_mul_f32_e32 v2, v42, v42
	v_fma_f32 v4, v42, v42, v2
	v_fma_f32 v5, v43, v43, v2
	v_mul_f32_e32 v2, v44, v44
	v_fma_f32 v8, v44, v44, v2
	v_fma_f32 v9, v45, v45, v2
	v_mul_f32_e32 v4, v38, v38
	v_mul_f32_e32 v8, v39, v39
	v_mul_f32_e32 v2, v40, v40
	v_mul_f32_e32 v6, v41, v41
	v_add_f32_e32 v4, v4, v8
	v_add_f32_e32 v5, v5, v9
	v_add_f32_e32 v2, v2, v6
	v_add_f32_e32 v3, v3, v7
	s_ashr_i32 s8, s6, 12
	v_add_f32_e32 v2, v4, v2
	v_add_f32_e32 v3, v5, v3
	v_lshl_add_u64 v[72:73], v[36:37], 0, v[0:1]
	v_add_f32_e32 v2, v2, v3
	v_lshl_add_u64 v[36:37], v[36:37], 0, s[74:75]
	s_nop 0
	v_add_f32_dpp v2, v2, v2 quad_perm:[1,0,3,2] row_mask:0xf bank_mask:0xf bound_ctrl:1
	s_nop 1
	v_add_f32_dpp v2, v2, v2 quad_perm:[2,3,0,1] row_mask:0xf bank_mask:0xf bound_ctrl:1
	s_nop 1
	v_add_f32_dpp v2, v2, v2 row_half_mirror row_mask:0xf bank_mask:0xf bound_ctrl:1
	s_nop 1
	v_add_f32_dpp v2, v2, v2 row_mirror row_mask:0xf bank_mask:0xf bound_ctrl:1
	s_nop 0
	v_readlane_b32 s9, v2, 16
	v_readlane_b32 s11, v2, 48
	v_readlane_b32 s6, v2, 0
	v_readlane_b32 s7, v2, 32
	v_mov_b32_e32 v2, s9
	v_mov_b32_e32 v3, s11
	v_add_f32_e32 v2, s6, v2
	v_add_f32_e32 v3, s7, v3
	s_nop 0
	v_add_f32_e32 v2, v2, v3
	v_fmamk_f32 v2, v2, 0x3a000000, v252
	v_cmp_gt_f32_e32 vcc, s55, v2
	v_mul_f32_e32 v3, 0x4f800000, v2
	s_nop 0
	v_cndmask_b32_e32 v2, v2, v3, vcc
	v_sqrt_f32_e32 v3, v2
	s_nop 0
	v_add_u32_e32 v4, -1, v3
	v_fma_f32 v5, -v4, v3, v2
	v_cmp_ge_f32_e64 s[6:7], 0, v5
	v_add_u32_e32 v5, 1, v3
	s_nop 0
	v_cndmask_b32_e64 v4, v3, v4, s[6:7]
	v_fma_f32 v3, -v5, v3, v2
	v_cmp_lt_f32_e64 s[6:7], 0, v3
	s_nop 1
	v_cndmask_b32_e64 v3, v4, v5, s[6:7]
	v_mul_f32_e32 v4, 0x37800000, v3
	v_cndmask_b32_e32 v3, v3, v4, vcc
	v_cmp_class_f32_e32 vcc, v2, v253
	s_nop 1
	v_cndmask_b32_e32 v2, v3, v2, vcc
	v_div_scale_f32 v3, s[6:7], v2, v2, 1.0
	v_rcp_f32_e32 v4, v3
	s_mul_hi_i32 s7, s8, 0xc000
	s_mul_i32 s8, s8, 0xc000
	s_add_u32 s6, s86, s8
	v_fma_f32 v5, -v3, v4, 1.0
	v_fmac_f32_e32 v4, v5, v4
	v_div_scale_f32 v5, vcc, 1.0, v2, 1.0
	v_mul_f32_e32 v6, v5, v4
	v_fma_f32 v7, -v3, v6, v5
	v_fmac_f32_e32 v6, v7, v4
	v_fma_f32 v3, -v3, v6, v5
	s_addc_u32 s7, s87, s7
	v_div_fmas_f32 v3, v3, v4, v6
	s_add_u32 s8, s6, 0x2000
	v_div_fixup_f32 v70, v3, v2, 1.0
	s_addc_u32 s9, s7, 0
	global_load_dwordx4 v[6:9], v[16:17], off
	global_load_dwordx4 v[2:5], v15, s[6:7]
	global_load_dwordx4 v[10:13], v15, s[8:9]
	v_mul_f32_e32 v68, v68, v70
	v_mul_f32_e32 v69, v69, v70
	v_mul_f32_e32 v66, v66, v70
	v_mul_f32_e32 v67, v67, v70
	v_mul_f32_e32 v64, v64, v70
	v_mul_f32_e32 v65, v65, v70
	v_mul_f32_e32 v62, v62, v70
	v_mul_f32_e32 v63, v63, v70
	v_mul_f32_e32 v60, v60, v70
	v_mul_f32_e32 v61, v61, v70
	v_mul_f32_e32 v58, v58, v70
	v_mul_f32_e32 v59, v59, v70
	v_mul_f32_e32 v56, v56, v70
	v_mul_f32_e32 v57, v57, v70
	v_mul_f32_e32 v54, v54, v70
	v_mul_f32_e32 v55, v55, v70
	v_mul_f32_e32 v52, v52, v70
	v_mul_f32_e32 v53, v53, v70
	v_mul_f32_e32 v50, v50, v70
	v_mul_f32_e32 v51, v51, v70
	v_mul_f32_e32 v48, v48, v70
	v_mul_f32_e32 v49, v49, v70
	v_mul_f32_e32 v46, v46, v70
	v_mul_f32_e32 v47, v47, v70
	v_mul_f32_e32 v44, v44, v70
	v_mul_f32_e32 v45, v45, v70
	v_mul_f32_e32 v42, v42, v70
	v_mul_f32_e32 v43, v43, v70
	v_mul_f32_e32 v40, v40, v70
	v_mul_f32_e32 v41, v41, v70
	v_mul_f32_e32 v38, v38, v70
	v_mul_f32_e32 v39, v39, v70
	s_add_i32 s10, s10, s42
	s_cmpk_lt_i32 s10, 0x4400
	s_waitcnt vmcnt(2)
	v_mul_f32_e32 v6, v6, v66
	v_mul_f32_e32 v7, v7, v67
	v_mul_f32_e32 v8, v8, v68
	v_mul_f32_e32 v9, v9, v69
	s_waitcnt vmcnt(0)
	v_add_f32_e32 v12, 1.0, v12
	v_add_f32_e32 v13, 1.0, v13
	v_add_f32_e32 v10, 1.0, v10
	v_add_f32_e32 v11, 1.0, v11
	v_fma_f32 v4, v12, v8, v4
	v_fma_f32 v5, v13, v9, v5
	v_fma_f32 v2, v10, v6, v2
	v_fma_f32 v3, v11, v7, v3
	s_nop 0
	v_cvt_pk_bf16_f32 v2, v2, v3
	v_cvt_pk_bf16_f32 v3, v4, v5
	global_store_dwordx2 v[72:73], v[2:3], off
	global_load_dwordx4 v[2:5], v[16:17], off offset:1024
	s_nop 0
	global_load_dwordx4 v[6:9], v15, s[6:7] offset:1024
	global_load_dwordx4 v[10:13], v78, s[8:9]
	s_waitcnt vmcnt(2)
; #define GAS __attribute__((address_space(1)))
; __device__ __forceinline__ unsigned pk2(float lo, float hi) { const f32x2_t v = {lo, hi}; const bf16x2_t b = __builtin_convertvector(v, bf16x2_t); return __builtin_bit_cast(unsigned, b); }
; __device__ __forceinline__ void norm_mod_phase(const Args& a, Frame& F, const float* gain, const float* modl, int sh_off, int sc_off, int nrows, const float* slab_gate) {
;     ...
; #pragma unroll
;         for (int j = 0; j < 8; ++j) { const int c = 256 * j + 4 * F.lane;
;             const f32x4 g = *(const GAS f32x4*)(gain + c), sh = *(const GAS f32x4*)(mb + sh_off + c), sc = *(const GAS f32x4*)(mb + sc_off + c);
;             const f32x4 y = (v[j] * rstd) * g * (sc + 1.0f) + sh;
;             v2u w; w.x = pk2(y[0], y[1]); w.y = pk2(y[2], y[3]); o8[64 * j] = w; }
	v_mul_f32_e32 v2, v2, v62
	v_mul_f32_e32 v3, v3, v63
	v_mul_f32_e32 v4, v4, v64
	v_mul_f32_e32 v5, v5, v65
	s_waitcnt vmcnt(0)
	v_add_f32_e32 v12, 1.0, v12
	v_add_f32_e32 v13, 1.0, v13
	v_add_f32_e32 v10, 1.0, v10
	v_add_f32_e32 v11, 1.0, v11
	v_fma_f32 v4, v12, v4, v8
	v_fma_f32 v5, v13, v5, v9
	v_fma_f32 v2, v10, v2, v6
	v_fma_f32 v3, v11, v3, v7
	s_nop 0
	v_cvt_pk_bf16_f32 v2, v2, v3
	v_cvt_pk_bf16_f32 v3, v4, v5
	global_store_dwordx2 v[72:73], v[2:3], off offset:512
	global_load_dwordx4 v[2:5], v[16:17], off offset:2048
	s_nop 0
	global_load_dwordx4 v[6:9], v15, s[6:7] offset:2048
	global_load_dwordx4 v[10:13], v79, s[8:9]
	s_waitcnt vmcnt(2)
	v_mul_f32_e32 v2, v2, v58
	v_mul_f32_e32 v3, v3, v59
	v_mul_f32_e32 v4, v4, v60
	v_mul_f32_e32 v5, v5, v61
	s_waitcnt vmcnt(0)
	v_add_f32_e32 v12, 1.0, v12
	v_add_f32_e32 v13, 1.0, v13
	v_add_f32_e32 v10, 1.0, v10
	v_add_f32_e32 v11, 1.0, v11
	v_fma_f32 v4, v4, v12, v8
	v_fma_f32 v5, v5, v13, v9
	v_fma_f32 v2, v2, v10, v6
	v_fma_f32 v3, v3, v11, v7
	s_nop 0
	v_cvt_pk_bf16_f32 v2, v2, v3
	v_cvt_pk_bf16_f32 v3, v4, v5
	global_store_dwordx2 v[72:73], v[2:3], off offset:1024
	global_load_dwordx4 v[2:5], v[16:17], off offset:3072
	s_nop 0
	global_load_dwordx4 v[6:9], v15, s[6:7] offset:3072
	global_load_dwordx4 v[10:13], v80, s[8:9]
	s_waitcnt vmcnt(2)
	v_mul_f32_e32 v2, v54, v2
	v_mul_f32_e32 v3, v55, v3
	v_mul_f32_e32 v4, v56, v4
	v_mul_f32_e32 v5, v57, v5
	s_waitcnt vmcnt(0)
	v_add_f32_e32 v12, 1.0, v12
	v_add_f32_e32 v13, 1.0, v13
	v_add_f32_e32 v10, 1.0, v10
	v_add_f32_e32 v11, 1.0, v11
	v_fma_f32 v4, v4, v12, v8
	v_fma_f32 v5, v5, v13, v9
	v_fma_f32 v2, v2, v10, v6
	v_fma_f32 v3, v3, v11, v7
	s_nop 0
	v_cvt_pk_bf16_f32 v2, v2, v3
	v_cvt_pk_bf16_f32 v3, v4, v5
	global_store_dwordx2 v[72:73], v[2:3], off offset:1536
	global_load_dwordx4 v[2:5], v[18:19], off
	s_nop 0
	global_load_dwordx4 v[6:9], v81, s[6:7]
	global_load_dwordx4 v[10:13], v81, s[8:9]
	s_waitcnt vmcnt(2)
	v_mul_f32_e32 v2, v50, v2
	v_mul_f32_e32 v3, v51, v3
	v_mul_f32_e32 v4, v52, v4
	v_mul_f32_e32 v5, v53, v5
	s_waitcnt vmcnt(0)
	v_add_f32_e32 v12, 1.0, v12
	v_add_f32_e32 v13, 1.0, v13
	v_add_f32_e32 v10, 1.0, v10
	v_add_f32_e32 v11, 1.0, v11
	v_fma_f32 v4, v4, v12, v8
	v_fma_f32 v5, v5, v13, v9
	v_fma_f32 v2, v2, v10, v6
	v_fma_f32 v3, v3, v11, v7
	s_nop 0
	v_cvt_pk_bf16_f32 v2, v2, v3
	v_cvt_pk_bf16_f32 v3, v4, v5
	global_store_dwordx2 v[72:73], v[2:3], off offset:2048
	global_load_dwordx4 v[2:5], v[20:21], off
	s_nop 0
	global_load_dwordx4 v[6:9], v82, s[6:7]
	global_load_dwordx4 v[10:13], v82, s[8:9]
	s_waitcnt vmcnt(2)
	v_mul_f32_e32 v2, v46, v2
	v_mul_f32_e32 v3, v47, v3
	v_mul_f32_e32 v4, v48, v4
	v_mul_f32_e32 v5, v49, v5
	s_waitcnt vmcnt(0)
	v_add_f32_e32 v12, 1.0, v12
	v_add_f32_e32 v13, 1.0, v13
	v_add_f32_e32 v10, 1.0, v10
	v_add_f32_e32 v11, 1.0, v11
	v_fma_f32 v4, v4, v12, v8
	v_fma_f32 v5, v5, v13, v9
	v_fma_f32 v2, v2, v10, v6
	v_fma_f32 v3, v3, v11, v7
	s_nop 0
	v_cvt_pk_bf16_f32 v2, v2, v3
	v_cvt_pk_bf16_f32 v3, v4, v5
	global_store_dwordx2 v[72:73], v[2:3], off offset:2560
	global_load_dwordx4 v[2:5], v[22:23], off
	s_nop 0
	global_load_dwordx4 v[6:9], v83, s[6:7]
	global_load_dwordx4 v[10:13], v83, s[8:9]
	s_waitcnt vmcnt(2)
	v_mul_f32_e32 v2, v42, v2
	v_mul_f32_e32 v3, v43, v3
	v_mul_f32_e32 v4, v44, v4
	v_mul_f32_e32 v5, v45, v5
	s_waitcnt vmcnt(0)
	v_add_f32_e32 v12, 1.0, v12
	v_add_f32_e32 v13, 1.0, v13
	v_add_f32_e32 v10, 1.0, v10
	v_add_f32_e32 v11, 1.0, v11
	v_fma_f32 v4, v4, v12, v8
	v_fma_f32 v5, v5, v13, v9
	v_fma_f32 v2, v2, v10, v6
	v_fma_f32 v3, v3, v11, v7
	s_nop 0
	v_cvt_pk_bf16_f32 v2, v2, v3
	v_cvt_pk_bf16_f32 v3, v4, v5
	global_store_dwordx2 v[72:73], v[2:3], off offset:3072
	global_load_dwordx4 v[2:5], v[24:25], off
	s_nop 0
	global_load_dwordx4 v[6:9], v84, s[6:7]
	global_load_dwordx4 v[10:13], v84, s[8:9]
	s_waitcnt vmcnt(2)
	v_mul_f32_e32 v2, v38, v2
	v_mul_f32_e32 v3, v39, v3
	v_mul_f32_e32 v4, v40, v4
	v_mul_f32_e32 v5, v41, v5
	s_waitcnt vmcnt(0)
	v_add_f32_e32 v12, 1.0, v12
	v_add_f32_e32 v13, 1.0, v13
	v_add_f32_e32 v10, 1.0, v10
	v_add_f32_e32 v11, 1.0, v11
	v_fma_f32 v4, v4, v12, v8
	v_fma_f32 v5, v5, v13, v9
	v_fma_f32 v2, v2, v10, v6
	v_fma_f32 v3, v3, v11, v7
	s_nop 0
	v_cvt_pk_bf16_f32 v2, v2, v3
	v_cvt_pk_bf16_f32 v3, v4, v5
	global_store_dwordx2 v[72:73], v[2:3], off offset:3584
	s_cbranch_scc0 .LBB0_214
; #define GAS __attribute__((address_space(1)))
; __device__ __forceinline__ unsigned xpk2(float lo, float hi) { if (XRES_F16) { const f32x2_t v = {lo, hi}; const f16x2_t h = __builtin_convertvector(v, f16x2_t); return __builtin_bit_cast(unsigned, h); } return pk2(lo, hi); }
; __device__ __forceinline__ float xlo(unsigned w) { if (XRES_F16) { const f16x2_t h = __builtin_bit_cast(f16x2_t, w); return (float)h[0]; } return __builtin_bit_cast(float, w << 16); }
; __device__ __forceinline__ float xhi(unsigned w) { if (XRES_F16) { const f16x2_t h = __builtin_bit_cast(f16x2_t, w); return (float)h[1]; } return __builtin_bit_cast(float, w & 0xffff0000u); }
; __device__ __forceinline__ void norm_mod_phase(const Args& a, Frame& F, const float* gain, const float* modl, int sh_off, int sc_off, int nrows, const float* slab_gate) {
;     ...
;         const GAS v2u* xr = (const GAS v2u*)(X + (size_t)r * D) + F.lane;
;         f32x4 v[8]; float ss = 0.f;
; #pragma unroll
;         for (int j = 0; j < 8; ++j) { const v2u w = xr[64 * j]; v[j] = (f32x4){xlo(w.x), xhi(w.x), xlo(w.y), xhi(w.y)}; }
;         if (slab_gate != nullptr && r >= ML) {
;             const GAS f32x4* sl = (const GAS f32x4*)((const float*)(a.ws + WS_SLAB) + (size_t)(r - ML) * D) + F.lane;
; #pragma unroll
;             for (int j = 0; j < 8; ++j) { const f32x4 p = (sl[64 * j] + sl[64 * j + (size_t)MC * D / 4]) + (sl[64 * j + 2 * ((size_t)MC * D / 4)] + sl[64 * j + 3 * ((size_t)MC * D / 4)]);
;                 v[j] += *(const GAS f32x4*)(slab_gate + 256 * j + 4 * F.lane) * p; v2u w; w.x = xpk2(v[j][0], v[j][1]); w.y = xpk2(v[j][2], v[j][3]); ((GAS v2u*)(X + (size_t)r * D) + F.lane)[64 * j] = w;
;                 v[j] = (f32x4){xlo(w.x), xhi(w.x), xlo(w.y), xhi(w.y)}; }
.LBB0_212:
	v_lshl_add_u64 v[4:5], v[36:37], 0, v[0:1]
	v_lshl_add_u64 v[2:3], v[4:5], 0, s[52:53]
	v_add_co_u32_e32 v4, vcc, 0xf7800000, v4
	global_load_dwordx2 v[6:7], v[2:3], off offset:512
	global_load_dwordx2 v[8:9], v[2:3], off offset:1024
	global_load_dwordx2 v[10:11], v[2:3], off offset:1536
	global_load_dwordx2 v[12:13], v[2:3], off offset:2048
	global_load_dwordx2 v[38:39], v[2:3], off offset:2560
	v_addc_co_u32_e32 v5, vcc, -1, v5, vcc
	global_load_dwordx2 v[40:41], v[2:3], off offset:3072
	s_nop 0
	global_load_dwordx2 v[4:5], v[4:5], off
	s_nop 0
	global_load_dwordx2 v[70:71], v[2:3], off offset:3584
	s_cmpk_lt_i32 s10, 0x4000
	s_cselect_b64 s[6:7], -1, 0
	s_or_b64 s[6:7], s[4:5], s[6:7]
	s_and_b64 vcc, exec, s[6:7]
	s_waitcnt vmcnt(7)
	v_cvt_f32_f16_e32 v62, v6
	v_cvt_f32_f16_sdwa v63, v6 dst_sel:DWORD dst_unused:UNUSED_PAD src0_sel:WORD_1
	v_cvt_f32_f16_e32 v64, v7
	v_cvt_f32_f16_sdwa v65, v7 dst_sel:DWORD dst_unused:UNUSED_PAD src0_sel:WORD_1
	s_waitcnt vmcnt(6)
	v_cvt_f32_f16_e32 v58, v8
	v_cvt_f32_f16_sdwa v59, v8 dst_sel:DWORD dst_unused:UNUSED_PAD src0_sel:WORD_1
	v_cvt_f32_f16_e32 v60, v9
	v_cvt_f32_f16_sdwa v61, v9 dst_sel:DWORD dst_unused:UNUSED_PAD src0_sel:WORD_1
	s_waitcnt vmcnt(5)
	v_cvt_f32_f16_e32 v54, v10
	v_cvt_f32_f16_sdwa v55, v10 dst_sel:DWORD dst_unused:UNUSED_PAD src0_sel:WORD_1
	v_cvt_f32_f16_e32 v56, v11
	v_cvt_f32_f16_sdwa v57, v11 dst_sel:DWORD dst_unused:UNUSED_PAD src0_sel:WORD_1
	s_waitcnt vmcnt(4)
	v_cvt_f32_f16_e32 v50, v12
	v_cvt_f32_f16_sdwa v51, v12 dst_sel:DWORD dst_unused:UNUSED_PAD src0_sel:WORD_1
	v_cvt_f32_f16_e32 v52, v13
	v_cvt_f32_f16_sdwa v53, v13 dst_sel:DWORD dst_unused:UNUSED_PAD src0_sel:WORD_1
	s_waitcnt vmcnt(3)
	v_cvt_f32_f16_e32 v46, v38
	v_cvt_f32_f16_sdwa v47, v38 dst_sel:DWORD dst_unused:UNUSED_PAD src0_sel:WORD_1
	v_cvt_f32_f16_e32 v48, v39
	v_cvt_f32_f16_sdwa v49, v39 dst_sel:DWORD dst_unused:UNUSED_PAD src0_sel:WORD_1
	s_waitcnt vmcnt(2)
	v_cvt_f32_f16_e32 v42, v40
	v_cvt_f32_f16_sdwa v43, v40 dst_sel:DWORD dst_unused:UNUSED_PAD src0_sel:WORD_1
	v_cvt_f32_f16_e32 v44, v41
	v_cvt_f32_f16_sdwa v45, v41 dst_sel:DWORD dst_unused:UNUSED_PAD src0_sel:WORD_1
	s_waitcnt vmcnt(1)
	v_cvt_f32_f16_e32 v66, v4
	v_cvt_f32_f16_sdwa v67, v4 dst_sel:DWORD dst_unused:UNUSED_PAD src0_sel:WORD_1
	v_cvt_f32_f16_e32 v68, v5
	v_cvt_f32_f16_sdwa v69, v5 dst_sel:DWORD dst_unused:UNUSED_PAD src0_sel:WORD_1
	s_waitcnt vmcnt(0)
	v_cvt_f32_f16_e32 v38, v70
	v_cvt_f32_f16_sdwa v39, v70 dst_sel:DWORD dst_unused:UNUSED_PAD src0_sel:WORD_1
	v_cvt_f32_f16_e32 v40, v71
	v_cvt_f32_f16_sdwa v41, v71 dst_sel:DWORD dst_unused:UNUSED_PAD src0_sel:WORD_1
	s_cbranch_vccnz .LBB0_211
	v_mov_b64_e32 v[4:5], s[0:1]
	flat_load_dwordx2 v[4:5], v[4:5] offset:152
	s_add_i32 s84, s10, 0xffffc000
	s_lshl_b64 s[6:7], s[84:85], 13
	v_lshlrev_b32_e32 v6, 4, v14
	v_mov_b32_e32 v7, v1
	s_waitcnt vmcnt(0) lgkmcnt(0)
	v_lshl_add_u64 v[4:5], v[4:5], 0, s[6:7]
	v_lshl_add_u64 v[90:91], v[4:5], 0, v[6:7]
	s_mov_b64 s[6:7], 0x58400000
	v_lshl_add_u64 v[12:13], v[90:91], 0, s[6:7]
	s_mov_b32 s6, 0x58401000
	v_add_co_u32_e32 v4, vcc, s6, v90
	s_mov_b32 s6, 0x58c00000
	s_nop 0
	v_addc_co_u32_e32 v5, vcc, 0, v91, vcc
	v_add_co_u32_e32 v70, vcc, s6, v90
	s_mov_b32 s6, 0x58c01000
	s_nop 0
	v_addc_co_u32_e32 v71, vcc, 0, v91, vcc
	v_add_co_u32_e32 v6, vcc, s6, v90
	global_load_dwordx4 v[8:11], v[4:5], off offset:-4096
	s_nop 0
	v_addc_co_u32_e32 v7, vcc, 0, v91, vcc
	global_load_dwordx4 v[86:89], v[6:7], off offset:-4096
	s_mov_b32 s6, 0x59400000
	v_add_co_u32_e32 v72, vcc, s6, v90
	s_mov_b32 s6, 0x59401000
	s_nop 0
	v_addc_co_u32_e32 v73, vcc, 0, v91, vcc
	s_waitcnt vmcnt(0)
	v_add_f32_e32 v96, v8, v86
	v_add_f32_e32 v97, v9, v87
	v_add_co_u32_e32 v8, vcc, s6, v90
	s_mov_b32 s6, 0x59c00000
	s_nop 0
	v_addc_co_u32_e32 v9, vcc, 0, v91, vcc
	v_add_co_u32_e32 v76, vcc, s6, v90
	s_mov_b32 s6, 0x59c01000
	s_nop 0
	v_addc_co_u32_e32 v77, vcc, 0, v91, vcc
	v_add_f32_e32 v94, v10, v88
	v_add_f32_e32 v95, v11, v89
	v_add_co_u32_e32 v10, vcc, s6, v90
	global_load_dwordx4 v[86:89], v[8:9], off offset:-4096
	s_nop 0
	v_addc_co_u32_e32 v11, vcc, 0, v91, vcc
	global_load_dwordx4 v[90:93], v[10:11], off offset:-4096
	s_waitcnt vmcnt(0)
	v_add_f32_e32 v88, v88, v92
	v_add_f32_e32 v89, v89, v93
	v_add_f32_e32 v86, v86, v90
	v_add_f32_e32 v87, v87, v91
	v_add_f32_e32 v90, v94, v88
	v_add_f32_e32 v91, v95, v89
	v_add_f32_e32 v92, v96, v86
	v_add_f32_e32 v93, v97, v87
	global_load_dwordx4 v[86:89], v[26:27], off
	s_waitcnt vmcnt(0)
	v_fma_f32 v68, v88, v90, v68
	v_fma_f32 v69, v89, v91, v69
	v_fma_f32 v66, v86, v92, v66
	v_fma_f32 v67, v87, v93, v67
	v_cvt_pk_f16_f32 v87, v68, v69
	v_cvt_pk_f16_f32 v86, v66, v67
	global_store_dwordx2 v[2:3], v[86:87], off
	v_cvt_f32_f16_e32 v66, v86
	v_cvt_f32_f16_sdwa v67, v86 dst_sel:DWORD dst_unused:UNUSED_PAD src0_sel:WORD_1
	v_cvt_f32_f16_e32 v68, v87
	v_cvt_f32_f16_sdwa v69, v87 dst_sel:DWORD dst_unused:UNUSED_PAD src0_sel:WORD_1
	global_load_dwordx4 v[86:89], v[12:13], off offset:1024
	global_load_dwordx4 v[90:93], v[70:71], off offset:1024
	s_waitcnt vmcnt(0)
	v_add_f32_e32 v94, v88, v92
	v_add_f32_e32 v95, v89, v93
	v_add_f32_e32 v96, v86, v90
	v_add_f32_e32 v97, v87, v91
	global_load_dwordx4 v[86:89], v[72:73], off offset:1024
	global_load_dwordx4 v[90:93], v[76:77], off offset:1024
	s_waitcnt vmcnt(0)
	v_add_f32_e32 v88, v88, v92
	v_add_f32_e32 v89, v89, v93
	v_add_f32_e32 v86, v86, v90
	v_add_f32_e32 v87, v87, v91
	v_add_f32_e32 v90, v94, v88
	v_add_f32_e32 v91, v95, v89
	v_add_f32_e32 v92, v96, v86
	v_add_f32_e32 v93, v97, v87
	global_load_dwordx4 v[86:89], v[26:27], off offset:1024
	s_waitcnt vmcnt(0)
; #define GAS __attribute__((address_space(1)))
; __device__ __forceinline__ unsigned xpk2(float lo, float hi) { if (XRES_F16) { const f32x2_t v = {lo, hi}; const f16x2_t h = __builtin_convertvector(v, f16x2_t); return __builtin_bit_cast(unsigned, h); } return pk2(lo, hi); }
; __device__ __forceinline__ float xlo(unsigned w) { if (XRES_F16) { const f16x2_t h = __builtin_bit_cast(f16x2_t, w); return (float)h[0]; } return __builtin_bit_cast(float, w << 16); }
; __device__ __forceinline__ float xhi(unsigned w) { if (XRES_F16) { const f16x2_t h = __builtin_bit_cast(f16x2_t, w); return (float)h[1]; } return __builtin_bit_cast(float, w & 0xffff0000u); }
; __device__ __forceinline__ void norm_mod_phase(const Args& a, Frame& F, const float* gain, const float* modl, int sh_off, int sc_off, int nrows, const float* slab_gate) {
;     ...
; #pragma unroll
;             for (int j = 0; j < 8; ++j) { const f32x4 p = (sl[64 * j] + sl[64 * j + (size_t)MC * D / 4]) + (sl[64 * j + 2 * ((size_t)MC * D / 4)] + sl[64 * j + 3 * ((size_t)MC * D / 4)]);
;                 v[j] += *(const GAS f32x4*)(slab_gate + 256 * j + 4 * F.lane) * p; v2u w; w.x = xpk2(v[j][0], v[j][1]); w.y = xpk2(v[j][2], v[j][3]); ((GAS v2u*)(X + (size_t)r * D) + F.lane)[64 * j] = w;
;                 v[j] = (f32x4){xlo(w.x), xhi(w.x), xlo(w.y), xhi(w.y)}; }
	v_fma_f32 v64, v88, v90, v64
	v_fma_f32 v65, v89, v91, v65
	v_fma_f32 v62, v86, v92, v62
	v_fma_f32 v63, v87, v93, v63
	v_cvt_pk_f16_f32 v87, v64, v65
	v_cvt_pk_f16_f32 v86, v62, v63
	global_store_dwordx2 v[2:3], v[86:87], off offset:512
	v_cvt_f32_f16_e32 v62, v86
	v_cvt_f32_f16_sdwa v63, v86 dst_sel:DWORD dst_unused:UNUSED_PAD src0_sel:WORD_1
	v_cvt_f32_f16_e32 v64, v87
	v_cvt_f32_f16_sdwa v65, v87 dst_sel:DWORD dst_unused:UNUSED_PAD src0_sel:WORD_1
	global_load_dwordx4 v[86:89], v[12:13], off offset:2048
	global_load_dwordx4 v[90:93], v[70:71], off offset:2048
	s_waitcnt vmcnt(0)
	v_add_f32_e32 v94, v88, v92
	v_add_f32_e32 v95, v89, v93
	v_add_f32_e32 v96, v86, v90
	v_add_f32_e32 v97, v87, v91
	global_load_dwordx4 v[86:89], v[72:73], off offset:2048
	global_load_dwordx4 v[90:93], v[76:77], off offset:2048
	s_waitcnt vmcnt(0)
	v_add_f32_e32 v88, v88, v92
	v_add_f32_e32 v89, v89, v93
	v_add_f32_e32 v86, v86, v90
	v_add_f32_e32 v87, v87, v91
	v_add_f32_e32 v90, v94, v88
	v_add_f32_e32 v91, v95, v89
	v_add_f32_e32 v92, v96, v86
	v_add_f32_e32 v93, v97, v87
	global_load_dwordx4 v[86:89], v[26:27], off offset:2048
	s_waitcnt vmcnt(0)
	v_fma_f32 v60, v88, v90, v60
	v_fma_f32 v61, v89, v91, v61
	v_fma_f32 v58, v86, v92, v58
	v_fma_f32 v59, v87, v93, v59
	v_cvt_pk_f16_f32 v87, v60, v61
	v_cvt_pk_f16_f32 v86, v58, v59
	global_store_dwordx2 v[2:3], v[86:87], off offset:1024
	v_cvt_f32_f16_e32 v58, v86
	v_cvt_f32_f16_sdwa v59, v86 dst_sel:DWORD dst_unused:UNUSED_PAD src0_sel:WORD_1
	v_cvt_f32_f16_e32 v60, v87
	v_cvt_f32_f16_sdwa v61, v87 dst_sel:DWORD dst_unused:UNUSED_PAD src0_sel:WORD_1
	global_load_dwordx4 v[86:89], v[12:13], off offset:3072
	global_load_dwordx4 v[90:93], v[70:71], off offset:3072
	s_waitcnt vmcnt(0)
	v_add_f32_e32 v12, v88, v92
	v_add_f32_e32 v13, v89, v93
	v_add_f32_e32 v90, v86, v90
	v_add_f32_e32 v91, v87, v91
	global_load_dwordx4 v[70:73], v[72:73], off offset:3072
	s_nop 0
	global_load_dwordx4 v[86:89], v[76:77], off offset:3072
	s_waitcnt vmcnt(0)
	v_add_f32_e32 v72, v72, v88
	v_add_f32_e32 v73, v73, v89
	v_add_f32_e32 v70, v70, v86
	v_add_f32_e32 v71, v71, v87
	v_add_f32_e32 v12, v12, v72
	v_add_f32_e32 v13, v13, v73
	v_add_f32_e32 v76, v90, v70
	v_add_f32_e32 v77, v91, v71
	global_load_dwordx4 v[70:73], v[26:27], off offset:3072
	s_waitcnt vmcnt(0)
	v_fma_f32 v12, v72, v12, v56
	v_fma_f32 v13, v73, v13, v57
	v_fma_f32 v54, v70, v76, v54
	v_fma_f32 v55, v71, v77, v55
	v_cvt_pk_f16_f32 v57, v12, v13
	v_cvt_pk_f16_f32 v56, v54, v55
	global_store_dwordx2 v[2:3], v[56:57], off offset:1536
	global_load_dwordx4 v[70:73], v[4:5], off
	global_load_dwordx4 v[86:89], v[6:7], off
	v_cvt_f32_f16_e32 v54, v56
	v_cvt_f32_f16_sdwa v55, v56 dst_sel:DWORD dst_unused:UNUSED_PAD src0_sel:WORD_1
	v_cvt_f32_f16_e32 v56, v57
	v_cvt_f32_f16_sdwa v57, v57 dst_sel:DWORD dst_unused:UNUSED_PAD src0_sel:WORD_1
	s_waitcnt vmcnt(0)
	v_add_f32_e32 v12, v72, v88
	v_add_f32_e32 v13, v73, v89
	v_add_f32_e32 v76, v70, v86
	v_add_f32_e32 v77, v71, v87
	global_load_dwordx4 v[70:73], v[8:9], off
	global_load_dwordx4 v[86:89], v[10:11], off
	s_waitcnt vmcnt(0)
	v_add_f32_e32 v72, v72, v88
	v_add_f32_e32 v73, v73, v89
	v_add_f32_e32 v70, v70, v86
	v_add_f32_e32 v71, v71, v87
	v_add_f32_e32 v12, v12, v72
	v_add_f32_e32 v13, v13, v73
	v_add_f32_e32 v76, v76, v70
	v_add_f32_e32 v77, v77, v71
	global_load_dwordx4 v[70:73], v[28:29], off
	s_waitcnt vmcnt(0)
; #define GAS __attribute__((address_space(1)))
; __device__ __forceinline__ unsigned xpk2(float lo, float hi) { if (XRES_F16) { const f32x2_t v = {lo, hi}; const f16x2_t h = __builtin_convertvector(v, f16x2_t); return __builtin_bit_cast(unsigned, h); } return pk2(lo, hi); }
; __device__ __forceinline__ float xlo(unsigned w) { if (XRES_F16) { const f16x2_t h = __builtin_bit_cast(f16x2_t, w); return (float)h[0]; } return __builtin_bit_cast(float, w << 16); }
; __device__ __forceinline__ float xhi(unsigned w) { if (XRES_F16) { const f16x2_t h = __builtin_bit_cast(f16x2_t, w); return (float)h[1]; } return __builtin_bit_cast(float, w & 0xffff0000u); }
; __device__ __forceinline__ void norm_mod_phase(const Args& a, Frame& F, const float* gain, const float* modl, int sh_off, int sc_off, int nrows, const float* slab_gate) {
;     ...
; #pragma unroll
;             for (int j = 0; j < 8; ++j) { const f32x4 p = (sl[64 * j] + sl[64 * j + (size_t)MC * D / 4]) + (sl[64 * j + 2 * ((size_t)MC * D / 4)] + sl[64 * j + 3 * ((size_t)MC * D / 4)]);
;                 v[j] += *(const GAS f32x4*)(slab_gate + 256 * j + 4 * F.lane) * p; v2u w; w.x = xpk2(v[j][0], v[j][1]); w.y = xpk2(v[j][2], v[j][3]); ((GAS v2u*)(X + (size_t)r * D) + F.lane)[64 * j] = w;
;                 v[j] = (f32x4){xlo(w.x), xhi(w.x), xlo(w.y), xhi(w.y)}; }
	v_fma_f32 v12, v72, v12, v52
	v_fma_f32 v13, v73, v13, v53
	v_fma_f32 v50, v70, v76, v50
	v_fma_f32 v51, v71, v77, v51
	v_cvt_pk_f16_f32 v53, v12, v13
	v_cvt_pk_f16_f32 v52, v50, v51
	global_store_dwordx2 v[2:3], v[52:53], off offset:2048
	global_load_dwordx4 v[70:73], v[4:5], off offset:1024
	global_load_dwordx4 v[86:89], v[6:7], off offset:1024
	v_cvt_f32_f16_e32 v50, v52
	v_cvt_f32_f16_sdwa v51, v52 dst_sel:DWORD dst_unused:UNUSED_PAD src0_sel:WORD_1
	v_cvt_f32_f16_e32 v52, v53
	v_cvt_f32_f16_sdwa v53, v53 dst_sel:DWORD dst_unused:UNUSED_PAD src0_sel:WORD_1
	s_waitcnt vmcnt(0)
	v_add_f32_e32 v12, v72, v88
	v_add_f32_e32 v13, v73, v89
	v_add_f32_e32 v76, v70, v86
	v_add_f32_e32 v77, v71, v87
	global_load_dwordx4 v[70:73], v[8:9], off offset:1024
	global_load_dwordx4 v[86:89], v[10:11], off offset:1024
	s_waitcnt vmcnt(0)
	v_add_f32_e32 v72, v72, v88
	v_add_f32_e32 v73, v73, v89
	v_add_f32_e32 v70, v70, v86
	v_add_f32_e32 v71, v71, v87
	v_add_f32_e32 v12, v12, v72
	v_add_f32_e32 v13, v13, v73
	v_add_f32_e32 v76, v76, v70
	v_add_f32_e32 v77, v77, v71
	global_load_dwordx4 v[70:73], v[30:31], off
	s_waitcnt vmcnt(0)
	v_fma_f32 v12, v72, v12, v48
	v_fma_f32 v13, v73, v13, v49
	v_fma_f32 v46, v70, v76, v46
	v_fma_f32 v47, v71, v77, v47
	v_cvt_pk_f16_f32 v49, v12, v13
	v_cvt_pk_f16_f32 v48, v46, v47
	global_store_dwordx2 v[2:3], v[48:49], off offset:2560
	global_load_dwordx4 v[70:73], v[4:5], off offset:2048
	global_load_dwordx4 v[86:89], v[6:7], off offset:2048
	v_cvt_f32_f16_e32 v46, v48
	v_cvt_f32_f16_sdwa v47, v48 dst_sel:DWORD dst_unused:UNUSED_PAD src0_sel:WORD_1
	v_cvt_f32_f16_e32 v48, v49
	v_cvt_f32_f16_sdwa v49, v49 dst_sel:DWORD dst_unused:UNUSED_PAD src0_sel:WORD_1
	s_waitcnt vmcnt(0)
	v_add_f32_e32 v12, v72, v88
	v_add_f32_e32 v13, v73, v89
	v_add_f32_e32 v76, v70, v86
	v_add_f32_e32 v77, v71, v87
	global_load_dwordx4 v[70:73], v[8:9], off offset:2048
	global_load_dwordx4 v[86:89], v[10:11], off offset:2048
	s_waitcnt vmcnt(0)
	v_add_f32_e32 v72, v72, v88
	v_add_f32_e32 v73, v73, v89
	v_add_f32_e32 v70, v70, v86
	v_add_f32_e32 v71, v71, v87
	v_add_f32_e32 v12, v12, v72
	v_add_f32_e32 v13, v13, v73
	v_add_f32_e32 v76, v76, v70
	v_add_f32_e32 v77, v77, v71
	global_load_dwordx4 v[70:73], v[32:33], off
	s_waitcnt vmcnt(0)
	v_fma_f32 v12, v72, v12, v44
	v_fma_f32 v13, v73, v13, v45
	v_fma_f32 v42, v70, v76, v42
	v_fma_f32 v43, v71, v77, v43
	v_cvt_pk_f16_f32 v45, v12, v13
	v_cvt_pk_f16_f32 v44, v42, v43
	global_store_dwordx2 v[2:3], v[44:45], off offset:3072
	global_load_dwordx4 v[70:73], v[4:5], off offset:3072
	s_nop 0
	global_load_dwordx4 v[4:7], v[6:7], off offset:3072
	v_cvt_f32_f16_e32 v42, v44
	v_cvt_f32_f16_sdwa v43, v44 dst_sel:DWORD dst_unused:UNUSED_PAD src0_sel:WORD_1
	v_cvt_f32_f16_e32 v44, v45
	v_cvt_f32_f16_sdwa v45, v45 dst_sel:DWORD dst_unused:UNUSED_PAD src0_sel:WORD_1
	s_waitcnt vmcnt(0)
	v_add_f32_e32 v12, v72, v6
	v_add_f32_e32 v13, v73, v7
	v_add_f32_e32 v70, v70, v4
	v_add_f32_e32 v71, v71, v5
	global_load_dwordx4 v[4:7], v[8:9], off offset:3072
	s_nop 0
	global_load_dwordx4 v[8:11], v[10:11], off offset:3072
	s_waitcnt vmcnt(0)
	v_add_f32_e32 v6, v6, v10
	v_add_f32_e32 v7, v7, v11
	v_add_f32_e32 v4, v4, v8
	v_add_f32_e32 v5, v5, v9
	v_add_f32_e32 v8, v12, v6
	v_add_f32_e32 v9, v13, v7
	v_add_f32_e32 v10, v70, v4
	v_add_f32_e32 v11, v71, v5
	global_load_dwordx4 v[4:7], v[34:35], off
	s_waitcnt vmcnt(0)
	v_fma_f32 v6, v6, v8, v40
	v_fma_f32 v7, v7, v9, v41
	v_fma_f32 v4, v4, v10, v38
	v_fma_f32 v5, v5, v11, v39
	s_nop 0
	v_cvt_pk_f16_f32 v4, v4, v5
	v_cvt_pk_f16_f32 v5, v6, v7
	v_cvt_f32_f16_e32 v38, v4
	v_cvt_f32_f16_sdwa v39, v4 dst_sel:DWORD dst_unused:UNUSED_PAD src0_sel:WORD_1
	v_cvt_f32_f16_e32 v40, v5
	v_cvt_f32_f16_sdwa v41, v5 dst_sel:DWORD dst_unused:UNUSED_PAD src0_sel:WORD_1
	global_store_dwordx2 v[2:3], v[4:5], off offset:3584
	s_branch .LBB0_211

; #define GAS __attribute__((address_space(1)))
; #define LAS __attribute__((address_space(3)))
; #define NR_LOAD(dst, k_) do { const GAS v2u* xr_ = (const GAS v2u*)(X + (size_t)(nw + 2048 * (k_)) * D) + F.lane; \
;         _Pragma("unroll") for (int j = 0; j < 8; ++j) dst[j] = __builtin_nontemporal_load(xr_ + 64 * j); } while (0)
; __device__ __forceinline__ void norm_mod_phase2(const Args& a, Frame& F, const float* gain, const float* modl, int sh_off, int sc_off, int nrows, const float* slab_gate) {
;     ...
;     const int nw = F.vcu * NWAVES + F.wave;
;     bf16* X = (bf16*)(a.ws + WS_X); bf16* HN = (bf16*)(a.ws + WS_HN);
;     LAS float* CA = (LAS float*)F.lds; LAS float* CB = CA + 5 * D;
;     v2u r0[8], r1[8], r2[8], r3[8], r4[8], r5[8], r6[8], r7[8];
;     ...
;     NR_LOAD(r0, 0); NR_LOAD(r1, 1); NR_LOAD(r2, 2); NR_LOAD(r3, 3); NR_LOAD(r4, 4); NR_LOAD(r5, 5); NR_LOAD(r6, 6); NR_LOAD(r7, 7);
;     { const GAS f32x4* g4 = (const GAS f32x4*)gain;
;       for (int q = F.tid; q < 5 * D / 4; q += NWAVES * 64) { const int bq = q >> 9, cq = q & 511; const GAS f32x4* mb4 = (const GAS f32x4*)(modl + (size_t)bq * MOD_LD);
;           ((LAS f32x4*)CA)[q] = g4[cq] * (mb4[sc_off / 4 + cq] + 1.0f); ((LAS f32x4*)CB)[q] = mb4[sh_off / 4 + cq]; } }
.LBB0_215:
	s_andn2_b64 vcc, exec, s[4:5]
	s_cbranch_vccnz .LBB0_224
	s_getreg_b32 s4, hwreg(HW_REG_HW_ID, 0, 6)
	s_lshl_b32 s4, s4, 2
	s_add_i32 s4, s4, 0
	s_add_i32 s4, s4, 0x20540
	v_mov_b32_e32 v0, s4
	ds_read_b32 v0, v0
	v_mov_b64_e32 v[2:3], s[0:1]
	v_mbcnt_lo_u32_b32 v4, -1, 0
	v_mbcnt_hi_u32_b32 v4, -1, v4
	s_mov_b64 s[20:21], 0x400000
	v_mov_b32_e32 v7, v1
	s_waitcnt lgkmcnt(0)
	v_readfirstlane_b32 s4, v0
	s_nop 1
	v_lshl_add_u32 v142, s4, 6, v4
	v_mov_b32_e32 v128, s72
	v_mov_b32_e32 v129, s73
	v_readfirstlane_b32 s4, v142
	s_ashr_i32 s4, s4, 6
	s_add_i32 s4, s4, s91
	s_ashr_i32 s5, s4, 31
	s_add_i32 s36, s4, 0x800
	s_add_i32 s30, s4, 0x1000
	s_add_i32 s26, s4, 0x1800
	s_add_i32 s22, s4, 0x2000
	s_add_i32 s18, s4, 0x2800
	v_and_b32_e32 v143, 63, v142
	s_lshl_b64 s[6:7], s[4:5], 12
	s_ashr_i32 s37, s36, 31
	s_ashr_i32 s31, s30, 31
	s_ashr_i32 s27, s26, 31
	s_ashr_i32 s23, s22, 31
	s_ashr_i32 s19, s18, 31
	v_lshlrev_b32_e32 v6, 3, v143
	s_lshl_b64 s[8:9], s[36:37], 12
	s_lshl_b64 s[10:11], s[30:31], 12
	s_lshl_b64 s[12:13], s[26:27], 12
	s_lshl_b64 s[14:15], s[22:23], 12
	s_lshl_b64 s[16:17], s[18:19], 12
	s_waitcnt vmcnt(0) lgkmcnt(0)
	v_lshl_add_u64 v[8:9], v[128:129], 0, s[20:21]
	v_lshl_add_u64 v[2:3], v[8:9], 0, s[6:7]
	v_lshl_add_u64 v[4:5], v[8:9], 0, s[8:9]
	v_lshl_add_u64 v[10:11], v[8:9], 0, s[10:11]
	v_lshl_add_u64 v[12:13], v[8:9], 0, s[12:13]
	v_lshl_add_u64 v[14:15], v[8:9], 0, s[14:15]
	v_lshl_add_u64 v[16:17], v[8:9], 0, s[16:17]
	v_lshl_add_u64 v[2:3], v[2:3], 0, v[6:7]
	v_lshl_add_u64 v[4:5], v[4:5], 0, v[6:7]
	v_lshl_add_u64 v[10:11], v[10:11], 0, v[6:7]
	v_lshl_add_u64 v[12:13], v[12:13], 0, v[6:7]
	v_lshl_add_u64 v[14:15], v[14:15], 0, v[6:7]
	v_lshl_add_u64 v[16:17], v[16:17], 0, v[6:7]
	v_and_b32_e32 v184, 0x1ff, v142
	v_lshlrev_b32_e32 v184, 4, v184
	v_mov_b32_e32 v185, 0
	v_mov_b32_e32 v186, s76
	v_lshlrev_b32_e32 v186, 13, v186
	v_mov_b32_e32 v187, 0
	v_lshl_add_u64 v[188:189], v[74:75], 0, v[186:187]
	v_lshl_add_u64 v[188:189], v[188:189], 0, v[184:185]
	global_load_dwordx4 v[192:195], v[188:189], off
	v_add_u32_e32 v196, 0x2000, v184
	v_mov_b32_e32 v201, v184
	v_add_u32_e32 v197, 0xe000, v184
	v_add_u32_e32 v202, 0xc000, v184
	v_add_u32_e32 v198, 0x1a000, v184
	v_add_u32_e32 v203, 0x18000, v184
	v_add_u32_e32 v199, 0x26000, v184
	v_add_u32_e32 v204, 0x24000, v184
	v_add_u32_e32 v200, 0x32000, v184
	v_add_u32_e32 v205, 0x30000, v184
	global_load_dwordx4 v[208:211], v196, s[86:87]
	global_load_dwordx4 v[228:231], v201, s[86:87]
	global_load_dwordx4 v[212:215], v197, s[86:87]
	global_load_dwordx4 v[232:235], v202, s[86:87]
	global_load_dwordx4 v[216:219], v198, s[86:87]
	global_load_dwordx4 v[236:239], v203, s[86:87]
	global_load_dwordx4 v[220:223], v199, s[86:87]
	global_load_dwordx4 v[240:243], v204, s[86:87]
	global_load_dwordx4 v[224:227], v200, s[86:87]
	global_load_dwordx4 v[244:247], v205, s[86:87]
	global_load_dwordx2 v[140:141], v[2:3], off nt
	global_load_dwordx2 v[138:139], v[2:3], off offset:512 nt
	global_load_dwordx2 v[136:137], v[2:3], off offset:1024 nt
	global_load_dwordx2 v[132:133], v[2:3], off offset:1536 nt
	global_load_dwordx2 v[134:135], v[2:3], off offset:2048 nt
	global_load_dwordx2 v[124:125], v[2:3], off offset:2560 nt
	global_load_dwordx2 v[126:127], v[2:3], off offset:3072 nt
	global_load_dwordx2 v[130:131], v[2:3], off offset:3584 nt
	global_load_dwordx2 v[122:123], v[4:5], off nt
	global_load_dwordx2 v[120:121], v[4:5], off offset:512 nt
	global_load_dwordx2 v[118:119], v[4:5], off offset:1024 nt
	global_load_dwordx2 v[116:117], v[4:5], off offset:1536 nt
	global_load_dwordx2 v[114:115], v[4:5], off offset:2048 nt
	global_load_dwordx2 v[112:113], v[4:5], off offset:2560 nt
	global_load_dwordx2 v[110:111], v[4:5], off offset:3072 nt
	global_load_dwordx2 v[108:109], v[4:5], off offset:3584 nt
	global_load_dwordx2 v[106:107], v[10:11], off nt
	global_load_dwordx2 v[104:105], v[10:11], off offset:512 nt
	global_load_dwordx2 v[102:103], v[10:11], off offset:1024 nt
	global_load_dwordx2 v[100:101], v[10:11], off offset:1536 nt
	global_load_dwordx2 v[98:99], v[10:11], off offset:2048 nt
	global_load_dwordx2 v[96:97], v[10:11], off offset:2560 nt
	global_load_dwordx2 v[94:95], v[10:11], off offset:3072 nt
	global_load_dwordx2 v[92:93], v[10:11], off offset:3584 nt
	global_load_dwordx2 v[90:91], v[12:13], off nt
	global_load_dwordx2 v[88:89], v[12:13], off offset:512 nt
	global_load_dwordx2 v[86:87], v[12:13], off offset:1024 nt
	global_load_dwordx2 v[84:85], v[12:13], off offset:1536 nt
	global_load_dwordx2 v[82:83], v[12:13], off offset:2048 nt
	global_load_dwordx2 v[80:81], v[12:13], off offset:2560 nt
	global_load_dwordx2 v[78:79], v[12:13], off offset:3072 nt
	global_load_dwordx2 v[76:77], v[12:13], off offset:3584 nt
	global_load_dwordx2 v[72:73], v[14:15], off nt
	global_load_dwordx2 v[70:71], v[14:15], off offset:512 nt
	global_load_dwordx2 v[68:69], v[14:15], off offset:1024 nt
	global_load_dwordx2 v[66:67], v[14:15], off offset:1536 nt
	global_load_dwordx2 v[64:65], v[14:15], off offset:2048 nt
	global_load_dwordx2 v[62:63], v[14:15], off offset:2560 nt
	global_load_dwordx2 v[60:61], v[14:15], off offset:3072 nt
	global_load_dwordx2 v[58:59], v[14:15], off offset:3584 nt
	global_load_dwordx2 v[56:57], v[16:17], off nt
	global_load_dwordx2 v[54:55], v[16:17], off offset:512 nt
	global_load_dwordx2 v[52:53], v[16:17], off offset:1024 nt
	global_load_dwordx2 v[50:51], v[16:17], off offset:1536 nt
	global_load_dwordx2 v[48:49], v[16:17], off offset:2048 nt
	global_load_dwordx2 v[46:47], v[16:17], off offset:2560 nt
	global_load_dwordx2 v[44:45], v[16:17], off offset:3072 nt
	global_load_dwordx2 v[42:43], v[16:17], off offset:3584 nt
	s_add_i32 s14, s4, 0x3000
	s_ashr_i32 s15, s14, 31
	s_lshl_b64 s[6:7], s[14:15], 12
	s_add_i32 s10, s4, 0x3800
	v_lshl_add_u64 v[2:3], v[8:9], 0, s[6:7]
	s_ashr_i32 s11, s10, 31
	v_lshl_add_u64 v[2:3], v[2:3], 0, v[6:7]
	s_lshl_b64 s[6:7], s[10:11], 12
	global_load_dwordx2 v[40:41], v[2:3], off nt
	global_load_dwordx2 v[38:39], v[2:3], off offset:512 nt
	global_load_dwordx2 v[36:37], v[2:3], off offset:1024 nt
	global_load_dwordx2 v[34:35], v[2:3], off offset:1536 nt
	global_load_dwordx2 v[32:33], v[2:3], off offset:2048 nt
	global_load_dwordx2 v[30:31], v[2:3], off offset:2560 nt
	global_load_dwordx2 v[28:29], v[2:3], off offset:3072 nt
	global_load_dwordx2 v[26:27], v[2:3], off offset:3584 nt
	v_lshl_add_u64 v[2:3], v[8:9], 0, s[6:7]
	v_lshl_add_u64 v[2:3], v[2:3], 0, v[6:7]
	global_load_dwordx2 v[24:25], v[2:3], off nt
	global_load_dwordx2 v[22:23], v[2:3], off offset:512 nt
	global_load_dwordx2 v[20:21], v[2:3], off offset:1024 nt
	global_load_dwordx2 v[18:19], v[2:3], off offset:1536 nt
	global_load_dwordx2 v[16:17], v[2:3], off offset:2048 nt
	global_load_dwordx2 v[14:15], v[2:3], off offset:2560 nt
	global_load_dwordx2 v[12:13], v[2:3], off offset:3072 nt
	global_load_dwordx2 v[10:11], v[2:3], off offset:3584 nt
	s_waitcnt vmcnt(62)
; #define GAS __attribute__((address_space(1)))
; #define LAS __attribute__((address_space(3)))
; __device__ __forceinline__ void norm_mod_phase2(const Args& a, Frame& F, const float* gain, const float* modl, int sh_off, int sc_off, int nrows, const float* slab_gate) {
;     ...
;     { const GAS f32x4* g4 = (const GAS f32x4*)gain;
;       for (int q = F.tid; q < 5 * D / 4; q += NWAVES * 64) { const int bq = q >> 9, cq = q & 511; const GAS f32x4* mb4 = (const GAS f32x4*)(modl + (size_t)bq * MOD_LD);
;           ((LAS f32x4*)CA)[q] = g4[cq] * (mb4[sc_off / 4 + cq] + 1.0f); ((LAS f32x4*)CB)[q] = mb4[sh_off / 4 + cq]; } }
;     asm volatile("s_waitcnt lgkmcnt(0)" ::: "memory"); __builtin_amdgcn_s_barrier(); asm volatile("" ::: "memory");
	v_lshl_add_u32 v184, v142, 4, 0
	v_add_u32_e32 v185, 0xa000, v184
	v_add_f32_e32 v210, 1.0, v210
	v_add_f32_e32 v211, 1.0, v211
	v_add_f32_e32 v208, 1.0, v208
	v_add_f32_e32 v209, 1.0, v209
	v_mul_f32_e32 v210, v194, v210
	v_mul_f32_e32 v211, v195, v211
	v_mul_f32_e32 v208, v192, v208
	v_mul_f32_e32 v209, v193, v209
	ds_write_b128 v184, v[208:211]
	ds_write_b128 v185, v[228:231]
	v_add_f32_e32 v214, 1.0, v214
	v_add_f32_e32 v215, 1.0, v215
	v_add_f32_e32 v212, 1.0, v212
	v_add_f32_e32 v213, 1.0, v213
	v_mul_f32_e32 v214, v194, v214
	v_mul_f32_e32 v215, v195, v215
	v_mul_f32_e32 v212, v192, v212
	v_mul_f32_e32 v213, v193, v213
	ds_write_b128 v184, v[212:215] offset:8192
	ds_write_b128 v185, v[232:235] offset:8192
	v_add_f32_e32 v218, 1.0, v218
	v_add_f32_e32 v219, 1.0, v219
	v_add_f32_e32 v216, 1.0, v216
	v_add_f32_e32 v217, 1.0, v217
	v_mul_f32_e32 v218, v194, v218
	v_mul_f32_e32 v219, v195, v219
	v_mul_f32_e32 v216, v192, v216
	v_mul_f32_e32 v217, v193, v217
	ds_write_b128 v184, v[216:219] offset:16384
	ds_write_b128 v185, v[236:239] offset:16384
	v_add_f32_e32 v222, 1.0, v222
	v_add_f32_e32 v223, 1.0, v223
	v_add_f32_e32 v220, 1.0, v220
	v_add_f32_e32 v221, 1.0, v221
	v_mul_f32_e32 v222, v194, v222
	v_mul_f32_e32 v223, v195, v223
	v_mul_f32_e32 v220, v192, v220
	v_mul_f32_e32 v221, v193, v221
	ds_write_b128 v184, v[220:223] offset:24576
	ds_write_b128 v185, v[240:243] offset:24576
	v_add_f32_e32 v226, 1.0, v226
	v_add_f32_e32 v227, 1.0, v227
	v_add_f32_e32 v224, 1.0, v224
	v_add_f32_e32 v225, 1.0, v225
	v_mul_f32_e32 v226, v194, v226
	v_mul_f32_e32 v227, v195, v227
	v_mul_f32_e32 v224, v192, v224
	v_mul_f32_e32 v225, v193, v225
	ds_write_b128 v184, v[224:227] offset:32768
	ds_write_b128 v185, v[244:247] offset:32768
	s_waitcnt vmcnt(62)
	v_cvt_f32_f16_sdwa v153, v140 dst_sel:DWORD dst_unused:UNUSED_PAD src0_sel:WORD_1
	v_cvt_f32_f16_sdwa v149, v138 dst_sel:DWORD dst_unused:UNUSED_PAD src0_sel:WORD_1
	v_cvt_f32_f16_e32 v152, v140
	v_cvt_f32_f16_sdwa v155, v141 dst_sel:DWORD dst_unused:UNUSED_PAD src0_sel:WORD_1
	v_cvt_f32_f16_e32 v148, v138
	v_cvt_f32_f16_sdwa v151, v139 dst_sel:DWORD dst_unused:UNUSED_PAD src0_sel:WORD_1
	v_cvt_f32_f16_e32 v154, v141
	v_cvt_f32_f16_e32 v150, v139
	s_waitcnt vmcnt(61)
	v_cvt_f32_f16_sdwa v139, v136 dst_sel:DWORD dst_unused:UNUSED_PAD src0_sel:WORD_1
	v_cvt_f32_f16_sdwa v141, v137 dst_sel:DWORD dst_unused:UNUSED_PAD src0_sel:WORD_1
	s_mov_b64 s[6:7], 0x8c00000
	v_mov_b32_e32 v74, v153
	v_mov_b32_e32 v75, v149
	v_cvt_f32_f16_e32 v138, v136
	v_cvt_f32_f16_e32 v140, v137
	v_lshl_add_u64 v[2:3], v[128:129], 0, s[6:7]
	v_mov_b32_e32 v4, v152
	v_mov_b32_e32 v5, v148
	v_mul_f32_e32 v74, v74, v74
	v_mul_f32_e32 v75, v75, v75
	v_mov_b32_e32 v128, v155
	v_mov_b32_e32 v129, v151
	v_fma_f32 v4, v4, v4, v74
	v_fma_f32 v5, v5, v5, v75
	v_mov_b32_e32 v74, v154
	v_mov_b32_e32 v75, v150
	v_mul_f32_e32 v128, v128, v128
	v_mul_f32_e32 v129, v129, v129
	s_waitcnt vmcnt(60)
	v_cvt_f32_f16_sdwa v145, v132 dst_sel:DWORD dst_unused:UNUSED_PAD src0_sel:WORD_1
	v_fma_f32 v74, v74, v74, v128
	v_fma_f32 v75, v75, v75, v129
	v_mov_b32_e32 v128, v139
	v_mov_b32_e32 v129, v141
	v_add_f32_e32 v4, v4, v74
	v_add_f32_e32 v5, v5, v75
	v_mov_b32_e32 v74, v138
	v_mov_b32_e32 v75, v140
	v_mul_f32_e32 v128, v128, v128
	v_mul_f32_e32 v129, v129, v129
	v_cvt_f32_f16_e32 v144, v132
	v_cvt_f32_f16_sdwa v147, v133 dst_sel:DWORD dst_unused:UNUSED_PAD src0_sel:WORD_1
	v_fma_f32 v74, v74, v74, v128
	v_fma_f32 v75, v75, v75, v129
	v_cvt_f32_f16_e32 v146, v133
	s_waitcnt vmcnt(59)
	v_cvt_f32_f16_sdwa v129, v134 dst_sel:DWORD dst_unused:UNUSED_PAD src0_sel:WORD_1
	v_cvt_f32_f16_e32 v128, v134
	v_cvt_f32_f16_sdwa v133, v135 dst_sel:DWORD dst_unused:UNUSED_PAD src0_sel:WORD_1
	v_cvt_f32_f16_e32 v132, v135
	v_mul_f32_e32 v0, v145, v145
	v_fma_f32 v136, v144, v144, v0
	v_fma_f32 v137, v145, v145, v0
	v_mul_f32_e32 v0, v147, v147
	v_pk_add_f32 v[4:5], v[4:5], v[4:5] op_sel:[0,1] op_sel_hi:[1,0]
	v_pk_add_f32 v[74:75], v[74:75], v[74:75] op_sel:[0,1] op_sel_hi:[1,0]
	v_fma_f32 v156, v146, v146, v0
	v_fma_f32 v157, v147, v147, v0
	v_mul_f32_e32 v134, v128, v128
	v_mul_f32_e32 v135, v129, v129
	v_mul_f32_e32 v158, v132, v132
	v_mul_f32_e32 v159, v133, v133
	v_mov_b32_e32 v5, v134
	v_mov_b32_e32 v75, v135
	v_mov_b32_e32 v137, v158
	v_mov_b32_e32 v157, v159
	v_add_f32_e32 v4, v4, v74
	v_add_f32_e32 v5, v5, v75
	v_add_f32_e32 v74, v136, v156
	v_add_f32_e32 v75, v137, v157
	s_waitcnt vmcnt(58)
	v_cvt_f32_f16_sdwa v135, v124 dst_sel:DWORD dst_unused:UNUSED_PAD src0_sel:WORD_1
	v_cvt_f32_f16_sdwa v137, v125 dst_sel:DWORD dst_unused:UNUSED_PAD src0_sel:WORD_1
	v_cvt_f32_f16_e32 v134, v124
	v_cvt_f32_f16_e32 v136, v125
	v_add_f32_e32 v4, v4, v74
	v_add_f32_e32 v5, v5, v75
	v_mov_b32_e32 v74, v135
	v_mov_b32_e32 v75, v137
	v_add_f32_e32 v156, v4, v5
	v_add_f32_e32 v157, v5, v4
	v_mov_b32_e32 v4, v134
	v_mov_b32_e32 v5, v136
	v_mul_f32_e32 v74, v74, v74
	v_mul_f32_e32 v75, v75, v75
	s_waitcnt vmcnt(57)
	v_cvt_f32_f16_sdwa v125, v127 dst_sel:DWORD dst_unused:UNUSED_PAD src0_sel:WORD_1
	v_fma_f32 v4, v4, v4, v74
	v_fma_f32 v5, v5, v5, v75
	v_cvt_f32_f16_e32 v124, v127
	v_add_f32_e32 v158, v4, v5
	v_add_f32_e32 v159, v5, v4
	v_cvt_f32_f16_sdwa v5, v126 dst_sel:DWORD dst_unused:UNUSED_PAD src0_sel:WORD_1
	v_cvt_f32_f16_e32 v4, v126
	s_waitcnt vmcnt(56)
	v_cvt_f32_f16_sdwa v75, v130 dst_sel:DWORD dst_unused:UNUSED_PAD src0_sel:WORD_1
	v_cvt_f32_f16_e32 v74, v130
	v_cvt_f32_f16_sdwa v127, v131 dst_sel:DWORD dst_unused:UNUSED_PAD src0_sel:WORD_1
	v_cvt_f32_f16_e32 v126, v131
	v_mul_f32_e32 v0, v5, v5
	v_fma_f32 v160, v4, v4, v0
	v_fma_f32 v161, v5, v5, v0
	v_mul_f32_e32 v0, v125, v125
	v_fma_f32 v162, v124, v124, v0
	v_fma_f32 v163, v125, v125, v0
	v_mul_f32_e32 v130, v74, v74
	v_mul_f32_e32 v131, v75, v75
	v_mul_f32_e32 v164, v126, v126
	v_mul_f32_e32 v165, v127, v127
	v_mov_b32_e32 v157, v130
	v_mov_b32_e32 v159, v131
	v_mov_b32_e32 v161, v164
	v_mov_b32_e32 v163, v165
	v_add_f32_e32 v130, v156, v158
	v_add_f32_e32 v131, v157, v159
	v_add_f32_e32 v156, v160, v162
	v_add_f32_e32 v157, v161, v163
	s_lshl_b64 s[8:9], s[4:5], 11
	v_add_f32_e32 v130, v130, v156
	v_add_f32_e32 v131, v131, v157
	s_lshl_b64 s[12:13], s[10:11], 11
	v_add_f32_e32 v0, v130, v131
	s_waitcnt lgkmcnt(0)
	s_barrier
; template <int CTRL> __device__ __forceinline__ float dpp_mov(float v) { return __builtin_bit_cast(float, __builtin_amdgcn_update_dpp(0, __builtin_bit_cast(int, v), CTRL, 0xF, 0xF, true)); }
; __device__ __forceinline__ float wave_sum(float v) {
;     v += dpp_mov<0xB1>(v);
;     v += dpp_mov<0x4E>(v);
;     v += dpp_mov<0x141>(v);
;     v += dpp_mov<0x140>(v);
;     const int iv = __builtin_bit_cast(int, v);
;     const float a = __builtin_bit_cast(float, __builtin_amdgcn_readlane(iv, 0)), b = __builtin_bit_cast(float, __builtin_amdgcn_readlane(iv, 16));
;     const float c = __builtin_bit_cast(float, __builtin_amdgcn_readlane(iv, 32)), d = __builtin_bit_cast(float, __builtin_amdgcn_readlane(iv, 48));
;     return (a + b) + (c + d);
	s_lshl_b64 s[40:41], s[36:37], 11
	v_add_f32_dpp v0, v0, v0 quad_perm:[1,0,3,2] row_mask:0xf bank_mask:0xf bound_ctrl:1
	s_lshl_b64 s[34:35], s[30:31], 11
	s_lshl_b64 s[28:29], s[26:27], 11
	v_add_f32_dpp v0, v0, v0 quad_perm:[2,3,0,1] row_mask:0xf bank_mask:0xf bound_ctrl:1
	s_lshl_b64 s[24:25], s[22:23], 11
	s_lshl_b64 s[20:21], s[18:19], 11
	v_add_f32_dpp v0, v0, v0 row_half_mirror row_mask:0xf bank_mask:0xf bound_ctrl:1
	s_lshl_b64 s[16:17], s[14:15], 11
	s_nop 0
	v_add_f32_dpp v0, v0, v0 row_mirror row_mask:0xf bank_mask:0xf bound_ctrl:1
	s_nop 0
	v_readlane_b32 s5, v0, 16
	v_readlane_b32 s11, v0, 48
	v_readlane_b32 s6, v0, 0
	v_readlane_b32 s7, v0, 32
	v_mov_b32_e32 v130, s5
	v_mov_b32_e32 v131, s11
	v_add_f32_e32 v130, s6, v130
	v_add_f32_e32 v131, s7, v131
	s_lshl_b32 s5, s4, 1
	v_add_f32_e32 v0, v130, v131
	v_fmamk_f32 v0, v0, 0x3a000000, v252
	v_cmp_gt_f32_e32 vcc, s55, v0
	v_mul_f32_e32 v7, 0x4f800000, v0
	s_and_b32 s5, s5, 0xffffe000
	v_cndmask_b32_e32 v0, v0, v7, vcc
	v_sqrt_f32_e32 v7, v0
	s_add_i32 s5, s5, 0
	v_add_u32_e32 v130, -1, v7
	v_fma_f32 v131, -v130, v7, v0
	v_cmp_ge_f32_e64 s[6:7], 0, v131
	v_add_u32_e32 v131, 1, v7
	s_nop 0
	v_cndmask_b32_e64 v130, v7, v130, s[6:7]
	v_fma_f32 v7, -v131, v7, v0
	v_cmp_lt_f32_e64 s[6:7], 0, v7
	s_nop 1
	v_cndmask_b32_e64 v7, v130, v131, s[6:7]
	v_mul_f32_e32 v130, 0x37800000, v7
	v_cndmask_b32_e32 v7, v7, v130, vcc
	v_cmp_class_f32_e32 vcc, v0, v253
	s_nop 1
	v_cndmask_b32_e32 v0, v7, v0, vcc
	v_div_scale_f32 v7, s[6:7], v0, v0, 1.0
	v_rcp_f32_e32 v130, v7
	s_nop 0
	v_fma_f32 v131, -v7, v130, 1.0
	v_fmac_f32_e32 v130, v131, v130
	v_div_scale_f32 v131, vcc, 1.0, v0, 1.0
	v_mul_f32_e32 v142, v131, v130
	v_fma_f32 v156, -v7, v142, v131
	v_fmac_f32_e32 v142, v156, v130
	v_fma_f32 v7, -v7, v142, v131
	v_div_fmas_f32 v7, v7, v130, v142
	v_div_fixup_f32 v142, v7, v0, 1.0
	v_lshlrev_b32_e32 v0, 4, v143
	v_add_u32_e32 v164, s5, v0
	v_mul_f32_e32 v160, v152, v142
	v_mul_f32_e32 v161, v153, v142
	v_mul_f32_e32 v162, v154, v142
	v_mul_f32_e32 v163, v155, v142
	ds_read_b128 v[152:155], v164
	ds_read_b128 v[156:159], v164 offset:40960
	v_lshl_add_u64 v[130:131], s[8:9], 1, v[2:3]
	v_mov_b32_e32 v7, v1
	v_lshl_add_u64 v[130:131], v[130:131], 0, v[6:7]
	v_mul_f32_e32 v128, v128, v142
	v_mul_f32_e32 v129, v129, v142
	s_waitcnt lgkmcnt(0)
	v_fma_f32 v154, v154, v162, v158
	v_fma_f32 v155, v155, v163, v159
	v_fma_f32 v152, v152, v160, v156
	v_fma_f32 v153, v153, v161, v157
	v_mul_f32_e32 v156, v148, v142
	v_mul_f32_e32 v157, v149, v142
	v_cvt_pk_bf16_f32 v152, v152, v153
	v_cvt_pk_bf16_f32 v153, v154, v155
	global_store_dwordx2 v[130:131], v[152:153], off
	v_mul_f32_e32 v158, v150, v142
	v_mul_f32_e32 v159, v151, v142
	ds_read_b128 v[148:151], v164 offset:1024
	ds_read_b128 v[152:155], v164 offset:41984
	v_mul_f32_e32 v132, v132, v142
	v_mul_f32_e32 v133, v133, v142
	v_mul_f32_e32 v4, v4, v142
	v_mul_f32_e32 v5, v5, v142
	v_mul_f32_e32 v124, v124, v142
	v_mul_f32_e32 v125, v125, v142
	s_waitcnt lgkmcnt(0)
	v_fma_f32 v150, v150, v158, v154
	v_fma_f32 v151, v151, v159, v155
	v_fma_f32 v148, v148, v156, v152
	v_fma_f32 v149, v149, v157, v153
	v_mul_f32_e32 v152, v138, v142
	v_mul_f32_e32 v153, v139, v142
	v_cvt_pk_bf16_f32 v148, v148, v149
	v_cvt_pk_bf16_f32 v149, v150, v151
	global_store_dwordx2 v[130:131], v[148:149], off offset:512
	v_mul_f32_e32 v154, v140, v142
	v_mul_f32_e32 v155, v141, v142
	ds_read_b128 v[138:141], v164 offset:2048
	ds_read_b128 v[148:151], v164 offset:43008
	s_waitcnt lgkmcnt(0)
	v_fma_f32 v140, v140, v154, v150
	v_fma_f32 v141, v141, v155, v151
	v_fma_f32 v138, v138, v152, v148
	v_fma_f32 v139, v139, v153, v149
	v_mul_f32_e32 v148, v144, v142
	v_mul_f32_e32 v149, v145, v142
	v_cvt_pk_bf16_f32 v138, v138, v139
	v_cvt_pk_bf16_f32 v139, v140, v141
	global_store_dwordx2 v[130:131], v[138:139], off offset:1024
	v_mul_f32_e32 v150, v146, v142
	v_mul_f32_e32 v151, v147, v142
	ds_read_b128 v[138:141], v164 offset:3072
	ds_read_b128 v[144:147], v164 offset:44032
	s_waitcnt lgkmcnt(0)
	v_fma_f32 v140, v150, v140, v146
	v_fma_f32 v141, v151, v141, v147
	v_fma_f32 v138, v148, v138, v144
	v_fma_f32 v139, v149, v139, v145
	s_nop 0
	v_cvt_pk_bf16_f32 v138, v138, v139
	v_cvt_pk_bf16_f32 v139, v140, v141
	global_store_dwordx2 v[130:131], v[138:139], off offset:1536
	ds_read_b128 v[138:141], v164 offset:4096
	ds_read_b128 v[144:147], v164 offset:45056
	s_waitcnt lgkmcnt(0)
	v_fma_f32 v132, v132, v140, v146
	v_fma_f32 v133, v133, v141, v147
	v_fma_f32 v128, v128, v138, v144
	v_fma_f32 v129, v129, v139, v145
	v_mul_f32_e32 v140, v136, v142
	v_mul_f32_e32 v141, v137, v142
	v_cvt_pk_bf16_f32 v128, v128, v129
	v_cvt_pk_bf16_f32 v129, v132, v133
	global_store_dwordx2 v[130:131], v[128:129], off offset:2048
	v_mul_f32_e32 v128, v134, v142
	v_mul_f32_e32 v129, v135, v142
	ds_read_b128 v[132:135], v164 offset:5120
	ds_read_b128 v[136:139], v164 offset:46080
	s_waitcnt lgkmcnt(0)
	v_fma_f32 v134, v140, v134, v138
	v_fma_f32 v135, v141, v135, v139
	v_fma_f32 v128, v128, v132, v136
	v_fma_f32 v129, v129, v133, v137
	s_nop 0
	v_cvt_pk_bf16_f32 v128, v128, v129
	v_cvt_pk_bf16_f32 v129, v134, v135
	global_store_dwordx2 v[130:131], v[128:129], off offset:2560
	ds_read_b128 v[132:135], v164 offset:6144
	ds_read_b128 v[136:139], v164 offset:47104
	s_waitcnt vmcnt(58)
	v_cvt_f32_f16_sdwa v129, v117 dst_sel:DWORD dst_unused:UNUSED_PAD src0_sel:WORD_1
	v_cvt_f32_f16_e32 v128, v117
	s_waitcnt lgkmcnt(0)
	v_fma_f32 v124, v124, v134, v138
	v_fma_f32 v125, v125, v135, v139
	v_fma_f32 v4, v4, v132, v136
	v_fma_f32 v5, v5, v133, v137
	v_cvt_f32_f16_sdwa v137, v122 dst_sel:DWORD dst_unused:UNUSED_PAD src0_sel:WORD_1
	v_cvt_pk_bf16_f32 v4, v4, v5
	v_cvt_pk_bf16_f32 v5, v124, v125
	global_store_dwordx2 v[130:131], v[4:5], off offset:3072
	v_mul_f32_e32 v4, v74, v142
	v_mul_f32_e32 v5, v75, v142
	v_mul_f32_e32 v74, v126, v142
	v_mul_f32_e32 v75, v127, v142
	ds_read_b128 v[124:127], v164 offset:7168
	ds_read_b128 v[132:135], v164 offset:48128
	v_cvt_f32_f16_e32 v136, v122
	v_cvt_f32_f16_sdwa v139, v123 dst_sel:DWORD dst_unused:UNUSED_PAD src0_sel:WORD_1
	v_cvt_f32_f16_e32 v138, v123
	v_cvt_f32_f16_sdwa v123, v118 dst_sel:DWORD dst_unused:UNUSED_PAD src0_sel:WORD_1
	s_waitcnt lgkmcnt(0)
	v_fma_f32 v4, v4, v124, v132
	v_fma_f32 v5, v5, v125, v133
	v_cvt_f32_f16_sdwa v133, v120 dst_sel:DWORD dst_unused:UNUSED_PAD src0_sel:WORD_1
	v_fma_f32 v74, v74, v126, v134
	v_fma_f32 v75, v75, v127, v135
	v_cvt_f32_f16_e32 v132, v120
	v_cvt_f32_f16_sdwa v135, v121 dst_sel:DWORD dst_unused:UNUSED_PAD src0_sel:WORD_1
	v_cvt_f32_f16_e32 v134, v121
	v_cvt_f32_f16_sdwa v125, v119 dst_sel:DWORD dst_unused:UNUSED_PAD src0_sel:WORD_1
	v_cvt_f32_f16_sdwa v127, v116 dst_sel:DWORD dst_unused:UNUSED_PAD src0_sel:WORD_1
	v_cvt_pk_bf16_f32 v4, v4, v5
	v_cvt_pk_bf16_f32 v5, v74, v75
	v_mov_b32_e32 v74, v137
	v_mov_b32_e32 v75, v133
	v_cvt_f32_f16_e32 v122, v118
	v_cvt_f32_f16_e32 v124, v119
	v_cvt_f32_f16_e32 v126, v116
	global_store_dwordx2 v[130:131], v[4:5], off offset:3584
	v_mov_b32_e32 v4, v136
	v_mov_b32_e32 v5, v132
	v_mul_f32_e32 v74, v74, v74
	v_mul_f32_e32 v75, v75, v75
	v_mov_b32_e32 v120, v139
	v_mov_b32_e32 v121, v135
	v_fma_f32 v4, v4, v4, v74
	v_fma_f32 v5, v5, v5, v75
	v_mov_b32_e32 v74, v138
	v_mov_b32_e32 v75, v134
	v_mul_f32_e32 v120, v120, v120
	v_mul_f32_e32 v121, v121, v121
	v_mov_b32_e32 v118, v123
	v_fma_f32 v74, v74, v74, v120
	v_fma_f32 v75, v75, v75, v121
	v_mov_b32_e32 v119, v125
	v_mul_f32_e32 v116, v127, v127
	v_add_f32_e32 v4, v4, v74
	v_add_f32_e32 v5, v5, v75
	v_mov_b32_e32 v74, v122
	v_mov_b32_e32 v75, v124
	v_mul_f32_e32 v118, v118, v118
	v_mul_f32_e32 v119, v119, v119
	v_fma_f32 v120, v126, v126, v116
	v_fma_f32 v121, v127, v127, v116
	v_mul_f32_e32 v116, v129, v129
	v_fma_f32 v74, v74, v74, v118
	v_fma_f32 v75, v75, v75, v119
	v_fma_f32 v130, v128, v128, v116
	v_fma_f32 v131, v129, v129, v116
	s_waitcnt vmcnt(59)
	v_cvt_f32_f16_sdwa v117, v114 dst_sel:DWORD dst_unused:UNUSED_PAD src0_sel:WORD_1
	v_cvt_f32_f16_e32 v116, v114
	v_cvt_f32_f16_sdwa v119, v115 dst_sel:DWORD dst_unused:UNUSED_PAD src0_sel:WORD_1
	v_cvt_f32_f16_e32 v118, v115
	v_pk_add_f32 v[4:5], v[4:5], v[4:5] op_sel:[0,1] op_sel_hi:[1,0]
	v_pk_add_f32 v[74:75], v[74:75], v[74:75] op_sel:[0,1] op_sel_hi:[1,0]
	v_mul_f32_e32 v114, v116, v116
	v_mul_f32_e32 v115, v117, v117
	v_mul_f32_e32 v140, v118, v118
	v_mul_f32_e32 v141, v119, v119
	v_mov_b32_e32 v5, v114
	v_mov_b32_e32 v75, v115
	v_mov_b32_e32 v121, v140
	v_mov_b32_e32 v131, v141
	v_add_f32_e32 v4, v4, v74
	v_add_f32_e32 v5, v5, v75
	v_add_f32_e32 v74, v120, v130
	v_add_f32_e32 v75, v121, v131
	s_waitcnt vmcnt(58)
	v_cvt_f32_f16_sdwa v115, v112 dst_sel:DWORD dst_unused:UNUSED_PAD src0_sel:WORD_1
	v_cvt_f32_f16_sdwa v121, v113 dst_sel:DWORD dst_unused:UNUSED_PAD src0_sel:WORD_1
	v_cvt_f32_f16_e32 v114, v112
	v_cvt_f32_f16_e32 v120, v113
	v_add_f32_e32 v4, v4, v74
	v_add_f32_e32 v5, v5, v75
	v_mov_b32_e32 v74, v115
	v_mov_b32_e32 v75, v121
	v_add_f32_e32 v130, v4, v5
	v_add_f32_e32 v131, v5, v4
	v_mov_b32_e32 v4, v114
	v_mov_b32_e32 v5, v120
	v_mul_f32_e32 v74, v74, v74
	v_mul_f32_e32 v75, v75, v75
	s_waitcnt vmcnt(57)
	v_cvt_f32_f16_sdwa v113, v111 dst_sel:DWORD dst_unused:UNUSED_PAD src0_sel:WORD_1
	v_fma_f32 v4, v4, v4, v74
	v_fma_f32 v5, v5, v5, v75
	v_cvt_f32_f16_e32 v112, v111
	v_add_f32_e32 v140, v4, v5
	v_add_f32_e32 v141, v5, v4
	v_cvt_f32_f16_sdwa v5, v110 dst_sel:DWORD dst_unused:UNUSED_PAD src0_sel:WORD_1
	v_cvt_f32_f16_e32 v4, v110
	s_waitcnt vmcnt(56)
	v_cvt_f32_f16_sdwa v111, v109 dst_sel:DWORD dst_unused:UNUSED_PAD src0_sel:WORD_1
	v_cvt_f32_f16_e32 v110, v109
	v_mul_f32_e32 v74, v5, v5
	v_fma_f32 v144, v4, v4, v74
	v_fma_f32 v145, v5, v5, v74
	v_mul_f32_e32 v74, v113, v113
	v_fma_f32 v146, v112, v112, v74
	v_fma_f32 v147, v113, v113, v74
	v_cvt_f32_f16_sdwa v75, v108 dst_sel:DWORD dst_unused:UNUSED_PAD src0_sel:WORD_1
	v_cvt_f32_f16_e32 v74, v108
	v_mul_f32_e32 v148, v110, v110
	v_mul_f32_e32 v149, v111, v111
	v_mul_f32_e32 v108, v74, v74
	v_mul_f32_e32 v109, v75, v75
	s_nop 0
	v_mov_b32_e32 v131, v108
	v_mov_b32_e32 v141, v109
	v_mov_b32_e32 v145, v148
	v_mov_b32_e32 v147, v149
	v_add_f32_e32 v108, v130, v140
	v_add_f32_e32 v109, v131, v141
	v_add_f32_e32 v130, v144, v146
	v_add_f32_e32 v131, v145, v147
	s_nop 0
	v_add_f32_e32 v108, v108, v130
	v_add_f32_e32 v109, v109, v131
	s_nop 0
	v_add_f32_e32 v108, v108, v109
	s_nop 1
	v_add_f32_dpp v108, v108, v108 quad_perm:[1,0,3,2] row_mask:0xf bank_mask:0xf bound_ctrl:1
	s_nop 1
	v_add_f32_dpp v108, v108, v108 quad_perm:[2,3,0,1] row_mask:0xf bank_mask:0xf bound_ctrl:1
	s_nop 1
	v_add_f32_dpp v108, v108, v108 row_half_mirror row_mask:0xf bank_mask:0xf bound_ctrl:1
	s_nop 1
	v_add_f32_dpp v108, v108, v108 row_mirror row_mask:0xf bank_mask:0xf bound_ctrl:1
	s_nop 0
	v_readlane_b32 s5, v108, 16
	v_readlane_b32 s11, v108, 48
	v_readlane_b32 s6, v108, 0
	v_readlane_b32 s7, v108, 32
	v_mov_b32_e32 v108, s5
	v_mov_b32_e32 v109, s11
	v_add_f32_e32 v108, s6, v108
	v_add_f32_e32 v109, s7, v109
	s_lshl_b32 s5, s36, 1
	v_add_f32_e32 v108, v108, v109
	v_fmamk_f32 v108, v108, 0x3a000000, v252
	v_cmp_gt_f32_e32 vcc, s55, v108
	v_mul_f32_e32 v109, 0x4f800000, v108
	s_and_b32 s5, s5, 0xffffe000
	v_cndmask_b32_e32 v108, v108, v109, vcc
	v_sqrt_f32_e32 v109, v108
	s_add_i32 s5, s5, 0
	v_add_u32_e32 v130, -1, v109
	v_fma_f32 v131, -v130, v109, v108
	v_cmp_ge_f32_e64 s[6:7], 0, v131
	v_add_u32_e32 v131, 1, v109
	s_nop 0
	v_cndmask_b32_e64 v130, v109, v130, s[6:7]
	v_fma_f32 v109, -v131, v109, v108
	v_cmp_lt_f32_e64 s[6:7], 0, v109
	s_nop 1
	v_cndmask_b32_e64 v109, v130, v131, s[6:7]
	v_mul_f32_e32 v130, 0x37800000, v109
	v_cndmask_b32_e32 v109, v109, v130, vcc
	v_cmp_class_f32_e32 vcc, v108, v253
	s_nop 1
	v_cndmask_b32_e32 v108, v109, v108, vcc
	v_div_scale_f32 v109, s[6:7], v108, v108, 1.0
	v_rcp_f32_e32 v130, v109
	s_nop 0
	v_fma_f32 v131, -v109, v130, 1.0
	v_fmac_f32_e32 v130, v131, v130
	v_div_scale_f32 v131, vcc, 1.0, v108, 1.0
	v_mul_f32_e32 v140, v131, v130
	v_fma_f32 v141, -v109, v140, v131
	v_fmac_f32_e32 v140, v141, v130
	v_fma_f32 v109, -v109, v140, v131
	v_div_fmas_f32 v109, v109, v130, v140
	v_div_fixup_f32 v130, v109, v108, 1.0
	v_mul_f32_e32 v140, v136, v130
	v_mul_f32_e32 v141, v137, v130
	v_mul_f32_e32 v148, v138, v130
	v_mul_f32_e32 v149, v139, v130
	v_add_u32_e32 v131, s5, v0
	ds_read_b128 v[136:139], v131
	ds_read_b128 v[144:147], v131 offset:40960
	v_lshl_add_u64 v[108:109], s[40:41], 1, v[2:3]
	v_lshl_add_u64 v[108:109], v[108:109], 0, v[6:7]
	v_mul_f32_e32 v4, v4, v130
	v_mul_f32_e32 v5, v5, v130
	s_waitcnt lgkmcnt(0)
	v_fma_f32 v138, v138, v148, v146
	v_fma_f32 v139, v139, v149, v147
	v_fma_f32 v136, v136, v140, v144
	v_fma_f32 v137, v137, v141, v145
	v_mul_f32_e32 v140, v132, v130
	v_mul_f32_e32 v141, v133, v130
	v_cvt_pk_bf16_f32 v136, v136, v137
	v_cvt_pk_bf16_f32 v137, v138, v139
	global_store_dwordx2 v[108:109], v[136:137], off
	v_mul_f32_e32 v144, v134, v130
	v_mul_f32_e32 v145, v135, v130
	ds_read_b128 v[132:135], v131 offset:1024
	ds_read_b128 v[136:139], v131 offset:41984
	s_waitcnt lgkmcnt(0)
	v_fma_f32 v134, v134, v144, v138
	v_fma_f32 v135, v135, v145, v139
	v_fma_f32 v132, v132, v140, v136
	v_fma_f32 v133, v133, v141, v137
	v_mul_f32_e32 v136, v122, v130
	v_mul_f32_e32 v137, v123, v130
	v_cvt_pk_bf16_f32 v132, v132, v133
	v_cvt_pk_bf16_f32 v133, v134, v135
	global_store_dwordx2 v[108:109], v[132:133], off offset:512
	v_mul_f32_e32 v138, v124, v130
	v_mul_f32_e32 v139, v125, v130
	ds_read_b128 v[122:125], v131 offset:2048
	ds_read_b128 v[132:135], v131 offset:43008
	s_waitcnt lgkmcnt(0)
	v_fma_f32 v124, v124, v138, v134
	v_fma_f32 v125, v125, v139, v135
	v_fma_f32 v122, v122, v136, v132
	v_fma_f32 v123, v123, v137, v133
	v_mul_f32_e32 v132, v126, v130
	v_mul_f32_e32 v133, v127, v130
	v_cvt_pk_bf16_f32 v122, v122, v123
	v_cvt_pk_bf16_f32 v123, v124, v125
	global_store_dwordx2 v[108:109], v[122:123], off offset:1024
	v_mul_f32_e32 v134, v128, v130
	v_mul_f32_e32 v135, v129, v130
	ds_read_b128 v[122:125], v131 offset:3072
	ds_read_b128 v[126:129], v131 offset:44032
	s_waitcnt lgkmcnt(0)
	v_fma_f32 v124, v134, v124, v128
	v_fma_f32 v125, v135, v125, v129
	v_fma_f32 v122, v132, v122, v126
	v_fma_f32 v123, v133, v123, v127
	v_mul_f32_e32 v126, v116, v130
	v_mul_f32_e32 v127, v117, v130
	v_cvt_pk_bf16_f32 v122, v122, v123
	v_cvt_pk_bf16_f32 v123, v124, v125
	global_store_dwordx2 v[108:109], v[122:123], off offset:1536
	v_mul_f32_e32 v128, v118, v130
	v_mul_f32_e32 v129, v119, v130
	ds_read_b128 v[116:119], v131 offset:4096
	ds_read_b128 v[122:125], v131 offset:45056
	s_waitcnt lgkmcnt(0)
	v_fma_f32 v118, v128, v118, v124
	v_fma_f32 v119, v129, v119, v125
	v_fma_f32 v116, v126, v116, v122
	v_fma_f32 v117, v127, v117, v123
	v_mul_f32_e32 v122, v114, v130
	v_mul_f32_e32 v123, v115, v130
	v_cvt_pk_bf16_f32 v116, v116, v117
	v_cvt_pk_bf16_f32 v117, v118, v119
	global_store_dwordx2 v[108:109], v[116:117], off offset:2048
	v_mul_f32_e32 v124, v120, v130
	v_mul_f32_e32 v125, v121, v130
	ds_read_b128 v[114:117], v131 offset:5120
	ds_read_b128 v[118:121], v131 offset:46080
	s_waitcnt lgkmcnt(0)
	v_fma_f32 v116, v124, v116, v120
	v_fma_f32 v117, v125, v117, v121
	v_fma_f32 v114, v122, v114, v118
	v_fma_f32 v115, v123, v115, v119
	v_mul_f32_e32 v120, v112, v130
	v_mul_f32_e32 v121, v113, v130
	v_cvt_pk_bf16_f32 v114, v114, v115
	v_cvt_pk_bf16_f32 v115, v116, v117
	global_store_dwordx2 v[108:109], v[114:115], off offset:2560
	ds_read_b128 v[112:115], v131 offset:6144
	ds_read_b128 v[116:119], v131 offset:47104
	s_waitcnt vmcnt(61)
	v_cvt_f32_f16_sdwa v123, v107 dst_sel:DWORD dst_unused:UNUSED_PAD src0_sel:WORD_1
	v_cvt_f32_f16_e32 v122, v107
	s_waitcnt vmcnt(59)
	v_cvt_f32_f16_sdwa v107, v102 dst_sel:DWORD dst_unused:UNUSED_PAD src0_sel:WORD_1
	s_waitcnt lgkmcnt(0)
	v_fma_f32 v114, v120, v114, v118
	v_fma_f32 v115, v121, v115, v119
	v_fma_f32 v4, v4, v112, v116
	v_fma_f32 v5, v5, v113, v117
	v_cvt_f32_f16_sdwa v121, v106 dst_sel:DWORD dst_unused:UNUSED_PAD src0_sel:WORD_1
	v_cvt_pk_bf16_f32 v4, v4, v5
	v_cvt_pk_bf16_f32 v5, v114, v115
	global_store_dwordx2 v[108:109], v[4:5], off offset:3072
	v_mul_f32_e32 v4, v74, v130
	v_mul_f32_e32 v5, v75, v130
	v_mul_f32_e32 v74, v110, v130
	v_mul_f32_e32 v75, v111, v130
	ds_read_b128 v[110:113], v131 offset:7168
	ds_read_b128 v[114:117], v131 offset:48128
	v_cvt_f32_f16_e32 v120, v106
	v_cvt_f32_f16_sdwa v119, v105 dst_sel:DWORD dst_unused:UNUSED_PAD src0_sel:WORD_1
	v_cvt_f32_f16_e32 v118, v105
	v_cvt_f32_f16_e32 v106, v102
	s_waitcnt lgkmcnt(0)
	v_fma_f32 v74, v74, v112, v116
	v_fma_f32 v75, v75, v113, v117
	v_cvt_f32_f16_sdwa v117, v104 dst_sel:DWORD dst_unused:UNUSED_PAD src0_sel:WORD_1
	v_fma_f32 v4, v4, v110, v114
	v_fma_f32 v5, v5, v111, v115
	v_cvt_f32_f16_e32 v116, v104
	v_cvt_pk_bf16_f32 v4, v4, v5
	v_cvt_pk_bf16_f32 v5, v74, v75
	global_store_dwordx2 v[108:109], v[4:5], off offset:3584
	v_cvt_f32_f16_sdwa v109, v103 dst_sel:DWORD dst_unused:UNUSED_PAD src0_sel:WORD_1
	s_waitcnt vmcnt(60)
	v_cvt_f32_f16_sdwa v111, v100 dst_sel:DWORD dst_unused:UNUSED_PAD src0_sel:WORD_1
	v_mov_b32_e32 v74, v121
	v_mov_b32_e32 v75, v117
	v_cvt_f32_f16_e32 v108, v103
	v_cvt_f32_f16_e32 v110, v100
	v_cvt_f32_f16_sdwa v113, v101 dst_sel:DWORD dst_unused:UNUSED_PAD src0_sel:WORD_1
	v_mov_b32_e32 v4, v120
	v_mov_b32_e32 v5, v116
	v_mul_f32_e32 v74, v74, v74
	v_mul_f32_e32 v75, v75, v75
	v_mov_b32_e32 v104, v123
	v_mov_b32_e32 v105, v119
	v_cvt_f32_f16_e32 v112, v101
	v_fma_f32 v4, v4, v4, v74
	v_fma_f32 v5, v5, v5, v75
	v_mov_b32_e32 v74, v122
	v_mov_b32_e32 v75, v118
	v_mul_f32_e32 v104, v104, v104
	v_mul_f32_e32 v105, v105, v105
	v_mov_b32_e32 v102, v107
	v_fma_f32 v74, v74, v74, v104
	v_fma_f32 v75, v75, v75, v105
	v_mov_b32_e32 v103, v109
	v_mul_f32_e32 v100, v111, v111
	v_add_f32_e32 v4, v4, v74
	v_add_f32_e32 v5, v5, v75
	v_mov_b32_e32 v74, v106
	v_mov_b32_e32 v75, v108
	v_mul_f32_e32 v102, v102, v102
	v_mul_f32_e32 v103, v103, v103
	v_fma_f32 v104, v110, v110, v100
	v_fma_f32 v105, v111, v111, v100
	v_mul_f32_e32 v100, v113, v113
	v_fma_f32 v74, v74, v74, v102
	v_fma_f32 v75, v75, v75, v103
	v_fma_f32 v114, v112, v112, v100
	v_fma_f32 v115, v113, v113, v100
	s_waitcnt vmcnt(59)
	v_cvt_f32_f16_sdwa v101, v98 dst_sel:DWORD dst_unused:UNUSED_PAD src0_sel:WORD_1
	v_cvt_f32_f16_e32 v100, v98
	v_cvt_f32_f16_sdwa v103, v99 dst_sel:DWORD dst_unused:UNUSED_PAD src0_sel:WORD_1
	v_cvt_f32_f16_e32 v102, v99
	v_pk_add_f32 v[4:5], v[4:5], v[4:5] op_sel:[0,1] op_sel_hi:[1,0]
	v_pk_add_f32 v[74:75], v[74:75], v[74:75] op_sel:[0,1] op_sel_hi:[1,0]
	v_mul_f32_e32 v98, v100, v100
	v_mul_f32_e32 v99, v101, v101
	v_mul_f32_e32 v124, v102, v102
	v_mul_f32_e32 v125, v103, v103
	v_mov_b32_e32 v5, v98
	v_mov_b32_e32 v75, v99
	v_mov_b32_e32 v105, v124
	v_mov_b32_e32 v115, v125
	v_add_f32_e32 v4, v4, v74
	v_add_f32_e32 v5, v5, v75
	v_add_f32_e32 v74, v104, v114
	v_add_f32_e32 v75, v105, v115
	s_waitcnt vmcnt(58)
	v_cvt_f32_f16_sdwa v99, v96 dst_sel:DWORD dst_unused:UNUSED_PAD src0_sel:WORD_1
	v_cvt_f32_f16_sdwa v105, v97 dst_sel:DWORD dst_unused:UNUSED_PAD src0_sel:WORD_1
	v_cvt_f32_f16_e32 v98, v96
	v_cvt_f32_f16_e32 v104, v97
	v_add_f32_e32 v4, v4, v74
	v_add_f32_e32 v5, v5, v75
	v_mov_b32_e32 v74, v99
	v_mov_b32_e32 v75, v105
	v_add_f32_e32 v114, v4, v5
	v_add_f32_e32 v115, v5, v4
	v_mov_b32_e32 v4, v98
	v_mov_b32_e32 v5, v104
	v_mul_f32_e32 v74, v74, v74
	v_mul_f32_e32 v75, v75, v75
	s_waitcnt vmcnt(57)
	v_cvt_f32_f16_sdwa v97, v95 dst_sel:DWORD dst_unused:UNUSED_PAD src0_sel:WORD_1
	v_fma_f32 v4, v4, v4, v74
	v_fma_f32 v5, v5, v5, v75
	v_cvt_f32_f16_e32 v96, v95
	v_add_f32_e32 v124, v4, v5
	v_add_f32_e32 v125, v5, v4
	v_cvt_f32_f16_sdwa v5, v94 dst_sel:DWORD dst_unused:UNUSED_PAD src0_sel:WORD_1
	v_cvt_f32_f16_e32 v4, v94
	s_waitcnt vmcnt(56)
	v_cvt_f32_f16_sdwa v95, v93 dst_sel:DWORD dst_unused:UNUSED_PAD src0_sel:WORD_1
	v_cvt_f32_f16_e32 v94, v93
	v_mul_f32_e32 v74, v5, v5
	v_fma_f32 v126, v4, v4, v74
	v_fma_f32 v127, v5, v5, v74
	v_mul_f32_e32 v74, v97, v97
	v_fma_f32 v128, v96, v96, v74
	v_fma_f32 v129, v97, v97, v74
	v_cvt_f32_f16_sdwa v75, v92 dst_sel:DWORD dst_unused:UNUSED_PAD src0_sel:WORD_1
	v_cvt_f32_f16_e32 v74, v92
	v_mul_f32_e32 v130, v94, v94
	v_mul_f32_e32 v131, v95, v95
	v_mul_f32_e32 v92, v74, v74
	v_mul_f32_e32 v93, v75, v75
	s_nop 0
	v_mov_b32_e32 v115, v92
	v_mov_b32_e32 v125, v93
	v_mov_b32_e32 v127, v130
	v_mov_b32_e32 v129, v131
	v_add_f32_e32 v92, v114, v124
	v_add_f32_e32 v93, v115, v125
	v_add_f32_e32 v114, v126, v128
	v_add_f32_e32 v115, v127, v129
	s_nop 0
	v_add_f32_e32 v92, v92, v114
	v_add_f32_e32 v93, v93, v115
	s_nop 0
	v_add_f32_e32 v92, v92, v93
	s_nop 1
	v_add_f32_dpp v92, v92, v92 quad_perm:[1,0,3,2] row_mask:0xf bank_mask:0xf bound_ctrl:1
	s_nop 1
	v_add_f32_dpp v92, v92, v92 quad_perm:[2,3,0,1] row_mask:0xf bank_mask:0xf bound_ctrl:1
	s_nop 1
	v_add_f32_dpp v92, v92, v92 row_half_mirror row_mask:0xf bank_mask:0xf bound_ctrl:1
	s_nop 1
	v_add_f32_dpp v92, v92, v92 row_mirror row_mask:0xf bank_mask:0xf bound_ctrl:1
	s_nop 0
	v_readlane_b32 s5, v92, 16
	v_readlane_b32 s11, v92, 48
	v_readlane_b32 s6, v92, 0
	v_readlane_b32 s7, v92, 32
	v_mov_b32_e32 v92, s5
	v_mov_b32_e32 v93, s11
	v_add_f32_e32 v92, s6, v92
	v_add_f32_e32 v93, s7, v93
	s_lshl_b32 s5, s30, 1
	v_add_f32_e32 v92, v92, v93
	v_fmamk_f32 v92, v92, 0x3a000000, v252
	v_cmp_gt_f32_e32 vcc, s55, v92
	v_mul_f32_e32 v93, 0x4f800000, v92
	s_and_b32 s5, s5, 0xffffe000
	v_cndmask_b32_e32 v92, v92, v93, vcc
	v_sqrt_f32_e32 v93, v92
	s_add_i32 s5, s5, 0
	v_add_u32_e32 v114, -1, v93
	v_fma_f32 v115, -v114, v93, v92
	v_cmp_ge_f32_e64 s[6:7], 0, v115
	v_add_u32_e32 v115, 1, v93
	s_nop 0
	v_cndmask_b32_e64 v114, v93, v114, s[6:7]
	v_fma_f32 v93, -v115, v93, v92
	v_cmp_lt_f32_e64 s[6:7], 0, v93
	s_nop 1
	v_cndmask_b32_e64 v93, v114, v115, s[6:7]
	v_mul_f32_e32 v114, 0x37800000, v93
	v_cndmask_b32_e32 v93, v93, v114, vcc
	v_cmp_class_f32_e32 vcc, v92, v253
	s_nop 1
	v_cndmask_b32_e32 v92, v93, v92, vcc
	v_div_scale_f32 v93, s[6:7], v92, v92, 1.0
	v_rcp_f32_e32 v114, v93
	s_nop 0
	v_fma_f32 v115, -v93, v114, 1.0
	v_fmac_f32_e32 v114, v115, v114
	v_div_scale_f32 v115, vcc, 1.0, v92, 1.0
	v_mul_f32_e32 v124, v115, v114
	v_fma_f32 v125, -v93, v124, v115
	v_fmac_f32_e32 v124, v125, v114
	v_fma_f32 v93, -v93, v124, v115
	v_div_fmas_f32 v93, v93, v114, v124
	v_div_fixup_f32 v114, v93, v92, 1.0
	v_mul_f32_e32 v128, v120, v114
	v_mul_f32_e32 v129, v121, v114
	v_mul_f32_e32 v130, v122, v114
	v_mul_f32_e32 v131, v123, v114
	v_add_u32_e32 v115, s5, v0
	ds_read_b128 v[120:123], v115
	ds_read_b128 v[124:127], v115 offset:40960
	v_lshl_add_u64 v[92:93], s[34:35], 1, v[2:3]
	v_lshl_add_u64 v[92:93], v[92:93], 0, v[6:7]
	v_mul_f32_e32 v4, v4, v114
	v_mul_f32_e32 v5, v5, v114
	s_waitcnt lgkmcnt(0)
	v_fma_f32 v122, v122, v130, v126
	v_fma_f32 v123, v123, v131, v127
	v_fma_f32 v120, v120, v128, v124
	v_fma_f32 v121, v121, v129, v125
	v_mul_f32_e32 v124, v116, v114
	v_mul_f32_e32 v125, v117, v114
	v_cvt_pk_bf16_f32 v120, v120, v121
	v_cvt_pk_bf16_f32 v121, v122, v123
	global_store_dwordx2 v[92:93], v[120:121], off
	v_mul_f32_e32 v126, v118, v114
	v_mul_f32_e32 v127, v119, v114
	ds_read_b128 v[116:119], v115 offset:1024
	ds_read_b128 v[120:123], v115 offset:41984
	s_waitcnt lgkmcnt(0)
	v_fma_f32 v118, v118, v126, v122
	v_fma_f32 v119, v119, v127, v123
	v_fma_f32 v116, v116, v124, v120
	v_fma_f32 v117, v117, v125, v121
	v_mul_f32_e32 v120, v106, v114
	v_mul_f32_e32 v121, v107, v114
	v_cvt_pk_bf16_f32 v116, v116, v117
	v_cvt_pk_bf16_f32 v117, v118, v119
	global_store_dwordx2 v[92:93], v[116:117], off offset:512
	v_mul_f32_e32 v122, v108, v114
	v_mul_f32_e32 v123, v109, v114
	ds_read_b128 v[106:109], v115 offset:2048
	ds_read_b128 v[116:119], v115 offset:43008
	s_waitcnt lgkmcnt(0)
	v_fma_f32 v108, v108, v122, v118
	v_fma_f32 v109, v109, v123, v119
	v_fma_f32 v106, v106, v120, v116
	v_fma_f32 v107, v107, v121, v117
	v_mul_f32_e32 v116, v110, v114
	v_mul_f32_e32 v117, v111, v114
	v_cvt_pk_bf16_f32 v106, v106, v107
	v_cvt_pk_bf16_f32 v107, v108, v109
	global_store_dwordx2 v[92:93], v[106:107], off offset:1024
	v_mul_f32_e32 v118, v112, v114
	v_mul_f32_e32 v119, v113, v114
	ds_read_b128 v[106:109], v115 offset:3072
	ds_read_b128 v[110:113], v115 offset:44032
	s_waitcnt lgkmcnt(0)
	v_fma_f32 v108, v118, v108, v112
	v_fma_f32 v109, v119, v109, v113
	v_fma_f32 v106, v116, v106, v110
	v_fma_f32 v107, v117, v107, v111
	v_mul_f32_e32 v110, v100, v114
	v_mul_f32_e32 v111, v101, v114
	v_cvt_pk_bf16_f32 v106, v106, v107
	v_cvt_pk_bf16_f32 v107, v108, v109
	global_store_dwordx2 v[92:93], v[106:107], off offset:1536
	v_mul_f32_e32 v112, v102, v114
	v_mul_f32_e32 v113, v103, v114
	ds_read_b128 v[100:103], v115 offset:4096
	ds_read_b128 v[106:109], v115 offset:45056
	s_waitcnt lgkmcnt(0)
	v_fma_f32 v102, v112, v102, v108
	v_fma_f32 v103, v113, v103, v109
	v_fma_f32 v100, v110, v100, v106
	v_fma_f32 v101, v111, v101, v107
	v_mul_f32_e32 v106, v98, v114
	v_mul_f32_e32 v107, v99, v114
	v_cvt_pk_bf16_f32 v100, v100, v101
	v_cvt_pk_bf16_f32 v101, v102, v103
	global_store_dwordx2 v[92:93], v[100:101], off offset:2048
	v_mul_f32_e32 v108, v104, v114
	v_mul_f32_e32 v109, v105, v114
	ds_read_b128 v[98:101], v115 offset:5120
	ds_read_b128 v[102:105], v115 offset:46080
	s_waitcnt lgkmcnt(0)
	v_fma_f32 v100, v108, v100, v104
	v_fma_f32 v101, v109, v101, v105
	v_fma_f32 v98, v106, v98, v102
	v_fma_f32 v99, v107, v99, v103
	v_mul_f32_e32 v104, v96, v114
	v_mul_f32_e32 v105, v97, v114
	v_cvt_pk_bf16_f32 v98, v98, v99
	v_cvt_pk_bf16_f32 v99, v100, v101
	global_store_dwordx2 v[92:93], v[98:99], off offset:2560
	ds_read_b128 v[96:99], v115 offset:6144
	ds_read_b128 v[100:103], v115 offset:47104
	s_waitcnt vmcnt(61)
	v_cvt_f32_f16_sdwa v107, v91 dst_sel:DWORD dst_unused:UNUSED_PAD src0_sel:WORD_1
	v_cvt_f32_f16_e32 v106, v91
	s_waitcnt vmcnt(59)
	v_cvt_f32_f16_sdwa v91, v86 dst_sel:DWORD dst_unused:UNUSED_PAD src0_sel:WORD_1
	s_waitcnt lgkmcnt(0)
	v_fma_f32 v98, v104, v98, v102
	v_fma_f32 v99, v105, v99, v103
	v_fma_f32 v4, v4, v96, v100
	v_fma_f32 v5, v5, v97, v101
	v_cvt_f32_f16_sdwa v105, v90 dst_sel:DWORD dst_unused:UNUSED_PAD src0_sel:WORD_1
	v_cvt_pk_bf16_f32 v4, v4, v5
	v_cvt_pk_bf16_f32 v5, v98, v99
	global_store_dwordx2 v[92:93], v[4:5], off offset:3072
	v_mul_f32_e32 v4, v74, v114
	v_mul_f32_e32 v5, v75, v114
	v_mul_f32_e32 v74, v94, v114
	v_mul_f32_e32 v75, v95, v114
	ds_read_b128 v[94:97], v115 offset:7168
	ds_read_b128 v[98:101], v115 offset:48128
	v_cvt_f32_f16_e32 v104, v90
	v_cvt_f32_f16_sdwa v103, v89 dst_sel:DWORD dst_unused:UNUSED_PAD src0_sel:WORD_1
	v_cvt_f32_f16_e32 v102, v89
	v_cvt_f32_f16_e32 v90, v86
	s_waitcnt lgkmcnt(0)
	v_fma_f32 v74, v74, v96, v100
	v_fma_f32 v75, v75, v97, v101
	v_cvt_f32_f16_sdwa v101, v88 dst_sel:DWORD dst_unused:UNUSED_PAD src0_sel:WORD_1
	v_fma_f32 v4, v4, v94, v98
	v_fma_f32 v5, v5, v95, v99
	v_cvt_f32_f16_e32 v100, v88
	v_cvt_pk_bf16_f32 v4, v4, v5
	v_cvt_pk_bf16_f32 v5, v74, v75
	global_store_dwordx2 v[92:93], v[4:5], off offset:3584
	v_cvt_f32_f16_sdwa v93, v87 dst_sel:DWORD dst_unused:UNUSED_PAD src0_sel:WORD_1
	s_waitcnt vmcnt(60)
	v_cvt_f32_f16_sdwa v95, v84 dst_sel:DWORD dst_unused:UNUSED_PAD src0_sel:WORD_1
	v_mov_b32_e32 v74, v105
	v_mov_b32_e32 v75, v101
	v_cvt_f32_f16_e32 v92, v87
	v_cvt_f32_f16_e32 v94, v84
	v_cvt_f32_f16_sdwa v97, v85 dst_sel:DWORD dst_unused:UNUSED_PAD src0_sel:WORD_1
	v_mov_b32_e32 v4, v104
	v_mov_b32_e32 v5, v100
	v_mul_f32_e32 v74, v74, v74
	v_mul_f32_e32 v75, v75, v75
	v_mov_b32_e32 v88, v107
	v_mov_b32_e32 v89, v103
	v_cvt_f32_f16_e32 v96, v85
	v_fma_f32 v4, v4, v4, v74
	v_fma_f32 v5, v5, v5, v75
	v_mov_b32_e32 v74, v106
	v_mov_b32_e32 v75, v102
	v_mul_f32_e32 v88, v88, v88
	v_mul_f32_e32 v89, v89, v89
	v_mov_b32_e32 v86, v91
	v_fma_f32 v74, v74, v74, v88
	v_fma_f32 v75, v75, v75, v89
	v_mov_b32_e32 v87, v93
	v_mul_f32_e32 v84, v95, v95
	v_add_f32_e32 v4, v4, v74
	v_add_f32_e32 v5, v5, v75
	v_mov_b32_e32 v74, v90
	v_mov_b32_e32 v75, v92
	v_mul_f32_e32 v86, v86, v86
	v_mul_f32_e32 v87, v87, v87
	v_fma_f32 v88, v94, v94, v84
	v_fma_f32 v89, v95, v95, v84
	v_mul_f32_e32 v84, v97, v97
	v_fma_f32 v74, v74, v74, v86
	v_fma_f32 v75, v75, v75, v87
	v_fma_f32 v98, v96, v96, v84
	v_fma_f32 v99, v97, v97, v84
	s_waitcnt vmcnt(59)
	v_cvt_f32_f16_sdwa v85, v82 dst_sel:DWORD dst_unused:UNUSED_PAD src0_sel:WORD_1
	v_cvt_f32_f16_e32 v84, v82
	v_cvt_f32_f16_sdwa v87, v83 dst_sel:DWORD dst_unused:UNUSED_PAD src0_sel:WORD_1
	v_cvt_f32_f16_e32 v86, v83
	v_pk_add_f32 v[4:5], v[4:5], v[4:5] op_sel:[0,1] op_sel_hi:[1,0]
	v_pk_add_f32 v[74:75], v[74:75], v[74:75] op_sel:[0,1] op_sel_hi:[1,0]
	v_mul_f32_e32 v82, v84, v84
	v_mul_f32_e32 v83, v85, v85
	v_mul_f32_e32 v108, v86, v86
	v_mul_f32_e32 v109, v87, v87
	v_mov_b32_e32 v5, v82
	v_mov_b32_e32 v75, v83
	v_mov_b32_e32 v89, v108
	v_mov_b32_e32 v99, v109
	v_add_f32_e32 v4, v4, v74
	v_add_f32_e32 v5, v5, v75
	v_add_f32_e32 v74, v88, v98
	v_add_f32_e32 v75, v89, v99
	s_waitcnt vmcnt(58)
	v_cvt_f32_f16_sdwa v83, v80 dst_sel:DWORD dst_unused:UNUSED_PAD src0_sel:WORD_1
	v_cvt_f32_f16_sdwa v89, v81 dst_sel:DWORD dst_unused:UNUSED_PAD src0_sel:WORD_1
	v_cvt_f32_f16_e32 v82, v80
	v_cvt_f32_f16_e32 v88, v81
	v_add_f32_e32 v4, v4, v74
	v_add_f32_e32 v5, v5, v75
	v_mov_b32_e32 v74, v83
	v_mov_b32_e32 v75, v89
	v_add_f32_e32 v98, v4, v5
	v_add_f32_e32 v99, v5, v4
	v_mov_b32_e32 v4, v82
	v_mov_b32_e32 v5, v88
	v_mul_f32_e32 v74, v74, v74
	v_mul_f32_e32 v75, v75, v75
	s_waitcnt vmcnt(57)
	v_cvt_f32_f16_sdwa v81, v79 dst_sel:DWORD dst_unused:UNUSED_PAD src0_sel:WORD_1
	v_fma_f32 v4, v4, v4, v74
	v_fma_f32 v5, v5, v5, v75
	v_cvt_f32_f16_e32 v80, v79
	v_add_f32_e32 v108, v4, v5
	v_add_f32_e32 v109, v5, v4
	v_cvt_f32_f16_sdwa v5, v78 dst_sel:DWORD dst_unused:UNUSED_PAD src0_sel:WORD_1
	v_cvt_f32_f16_e32 v4, v78
	s_waitcnt vmcnt(56)
	v_cvt_f32_f16_sdwa v79, v77 dst_sel:DWORD dst_unused:UNUSED_PAD src0_sel:WORD_1
	v_cvt_f32_f16_e32 v78, v77
	v_mul_f32_e32 v74, v5, v5
	v_fma_f32 v110, v4, v4, v74
	v_fma_f32 v111, v5, v5, v74
	v_mul_f32_e32 v74, v81, v81
	v_fma_f32 v112, v80, v80, v74
	v_fma_f32 v113, v81, v81, v74
	v_cvt_f32_f16_sdwa v75, v76 dst_sel:DWORD dst_unused:UNUSED_PAD src0_sel:WORD_1
	v_cvt_f32_f16_e32 v74, v76
	v_mul_f32_e32 v114, v78, v78
	v_mul_f32_e32 v115, v79, v79
	v_mul_f32_e32 v76, v74, v74
	v_mul_f32_e32 v77, v75, v75
	s_nop 0
	v_mov_b32_e32 v99, v76
	v_mov_b32_e32 v109, v77
	v_mov_b32_e32 v111, v114
	v_mov_b32_e32 v113, v115
	v_add_f32_e32 v76, v98, v108
	v_add_f32_e32 v77, v99, v109
	v_add_f32_e32 v98, v110, v112
	v_add_f32_e32 v99, v111, v113
	s_nop 0
	v_add_f32_e32 v76, v76, v98
	v_add_f32_e32 v77, v77, v99
	s_nop 0
	v_add_f32_e32 v76, v76, v77
	s_nop 1
	v_add_f32_dpp v76, v76, v76 quad_perm:[1,0,3,2] row_mask:0xf bank_mask:0xf bound_ctrl:1
	s_nop 1
	v_add_f32_dpp v76, v76, v76 quad_perm:[2,3,0,1] row_mask:0xf bank_mask:0xf bound_ctrl:1
	s_nop 1
	v_add_f32_dpp v76, v76, v76 row_half_mirror row_mask:0xf bank_mask:0xf bound_ctrl:1
	s_nop 1
	v_add_f32_dpp v76, v76, v76 row_mirror row_mask:0xf bank_mask:0xf bound_ctrl:1
	s_nop 0
	v_readlane_b32 s5, v76, 16
	v_readlane_b32 s11, v76, 48
	v_readlane_b32 s6, v76, 0
	v_readlane_b32 s7, v76, 32
	v_mov_b32_e32 v76, s5
	v_mov_b32_e32 v77, s11
	v_add_f32_e32 v76, s6, v76
	v_add_f32_e32 v77, s7, v77
	s_lshl_b32 s5, s26, 1
	v_add_f32_e32 v76, v76, v77
	v_fmamk_f32 v76, v76, 0x3a000000, v252
	v_cmp_gt_f32_e32 vcc, s55, v76
	v_mul_f32_e32 v77, 0x4f800000, v76
	s_and_b32 s5, s5, 0xffffe000
	v_cndmask_b32_e32 v76, v76, v77, vcc
	v_sqrt_f32_e32 v77, v76
	s_add_i32 s5, s5, 0
	v_add_u32_e32 v98, -1, v77
	v_fma_f32 v99, -v98, v77, v76
	v_cmp_ge_f32_e64 s[6:7], 0, v99
	v_add_u32_e32 v99, 1, v77
	s_nop 0
	v_cndmask_b32_e64 v98, v77, v98, s[6:7]
	v_fma_f32 v77, -v99, v77, v76
	v_cmp_lt_f32_e64 s[6:7], 0, v77
	s_nop 1
	v_cndmask_b32_e64 v77, v98, v99, s[6:7]
	v_mul_f32_e32 v98, 0x37800000, v77
	v_cndmask_b32_e32 v77, v77, v98, vcc
	v_cmp_class_f32_e32 vcc, v76, v253
	s_nop 1
	v_cndmask_b32_e32 v76, v77, v76, vcc
	v_div_scale_f32 v77, s[6:7], v76, v76, 1.0
	v_rcp_f32_e32 v98, v77
	s_nop 0
	v_fma_f32 v99, -v77, v98, 1.0
	v_fmac_f32_e32 v98, v99, v98
	v_div_scale_f32 v99, vcc, 1.0, v76, 1.0
	v_mul_f32_e32 v108, v99, v98
	v_fma_f32 v109, -v77, v108, v99
	v_fmac_f32_e32 v108, v109, v98
	v_fma_f32 v77, -v77, v108, v99
	v_div_fmas_f32 v77, v77, v98, v108
	v_div_fixup_f32 v98, v77, v76, 1.0
	v_mul_f32_e32 v112, v104, v98
	v_mul_f32_e32 v113, v105, v98
	v_mul_f32_e32 v114, v106, v98
	v_mul_f32_e32 v115, v107, v98
	v_add_u32_e32 v99, s5, v0
	ds_read_b128 v[104:107], v99
	ds_read_b128 v[108:111], v99 offset:40960
	v_lshl_add_u64 v[76:77], s[28:29], 1, v[2:3]
	v_lshl_add_u64 v[76:77], v[76:77], 0, v[6:7]
	v_mul_f32_e32 v4, v4, v98
	v_mul_f32_e32 v5, v5, v98
	s_waitcnt lgkmcnt(0)
	v_fma_f32 v106, v106, v114, v110
	v_fma_f32 v107, v107, v115, v111
	v_fma_f32 v104, v104, v112, v108
	v_fma_f32 v105, v105, v113, v109
	v_mul_f32_e32 v108, v100, v98
	v_mul_f32_e32 v109, v101, v98
	v_cvt_pk_bf16_f32 v104, v104, v105
	v_cvt_pk_bf16_f32 v105, v106, v107
	global_store_dwordx2 v[76:77], v[104:105], off
	v_mul_f32_e32 v110, v102, v98
	v_mul_f32_e32 v111, v103, v98
	ds_read_b128 v[100:103], v99 offset:1024
	ds_read_b128 v[104:107], v99 offset:41984
	s_waitcnt lgkmcnt(0)
	v_fma_f32 v102, v102, v110, v106
	v_fma_f32 v103, v103, v111, v107
	v_fma_f32 v100, v100, v108, v104
	v_fma_f32 v101, v101, v109, v105
	v_mul_f32_e32 v104, v90, v98
	v_mul_f32_e32 v105, v91, v98
	v_cvt_pk_bf16_f32 v100, v100, v101
	v_cvt_pk_bf16_f32 v101, v102, v103
	global_store_dwordx2 v[76:77], v[100:101], off offset:512
	v_mul_f32_e32 v106, v92, v98
	v_mul_f32_e32 v107, v93, v98
	ds_read_b128 v[90:93], v99 offset:2048
	ds_read_b128 v[100:103], v99 offset:43008
	s_waitcnt lgkmcnt(0)
	v_fma_f32 v92, v92, v106, v102
	v_fma_f32 v93, v93, v107, v103
	v_fma_f32 v90, v90, v104, v100
	v_fma_f32 v91, v91, v105, v101
	v_mul_f32_e32 v100, v94, v98
	v_mul_f32_e32 v101, v95, v98
	v_cvt_pk_bf16_f32 v90, v90, v91
	v_cvt_pk_bf16_f32 v91, v92, v93
	global_store_dwordx2 v[76:77], v[90:91], off offset:1024
	v_mul_f32_e32 v102, v96, v98
	v_mul_f32_e32 v103, v97, v98
	ds_read_b128 v[90:93], v99 offset:3072
	ds_read_b128 v[94:97], v99 offset:44032
	s_waitcnt lgkmcnt(0)
	v_fma_f32 v92, v102, v92, v96
	v_fma_f32 v93, v103, v93, v97
	v_fma_f32 v90, v100, v90, v94
	v_fma_f32 v91, v101, v91, v95
	v_mul_f32_e32 v94, v84, v98
	v_mul_f32_e32 v95, v85, v98
	v_cvt_pk_bf16_f32 v90, v90, v91
	v_cvt_pk_bf16_f32 v91, v92, v93
	global_store_dwordx2 v[76:77], v[90:91], off offset:1536
	v_mul_f32_e32 v96, v86, v98
	v_mul_f32_e32 v97, v87, v98
	ds_read_b128 v[84:87], v99 offset:4096
	ds_read_b128 v[90:93], v99 offset:45056
	s_waitcnt lgkmcnt(0)
	v_fma_f32 v86, v96, v86, v92
	v_fma_f32 v87, v97, v87, v93
	v_fma_f32 v84, v94, v84, v90
	v_fma_f32 v85, v95, v85, v91
	v_mul_f32_e32 v90, v82, v98
	v_mul_f32_e32 v91, v83, v98
	v_cvt_pk_bf16_f32 v84, v84, v85
	v_cvt_pk_bf16_f32 v85, v86, v87
	global_store_dwordx2 v[76:77], v[84:85], off offset:2048
	v_mul_f32_e32 v92, v88, v98
	v_mul_f32_e32 v93, v89, v98
	ds_read_b128 v[82:85], v99 offset:5120
	ds_read_b128 v[86:89], v99 offset:46080
	s_waitcnt lgkmcnt(0)
	v_fma_f32 v84, v92, v84, v88
	v_fma_f32 v85, v93, v85, v89
	v_fma_f32 v82, v90, v82, v86
	v_fma_f32 v83, v91, v83, v87
	v_mul_f32_e32 v88, v80, v98
	v_mul_f32_e32 v89, v81, v98
	v_cvt_pk_bf16_f32 v82, v82, v83
	v_cvt_pk_bf16_f32 v83, v84, v85
	global_store_dwordx2 v[76:77], v[82:83], off offset:2560
	ds_read_b128 v[80:83], v99 offset:6144
	ds_read_b128 v[84:87], v99 offset:47104
	s_waitcnt vmcnt(61)
	v_cvt_f32_f16_sdwa v91, v73 dst_sel:DWORD dst_unused:UNUSED_PAD src0_sel:WORD_1
	v_cvt_f32_f16_e32 v90, v73
	s_waitcnt lgkmcnt(0)
	v_fma_f32 v82, v88, v82, v86
	v_fma_f32 v83, v89, v83, v87
	v_fma_f32 v4, v4, v80, v84
	v_fma_f32 v5, v5, v81, v85
	v_cvt_f32_f16_sdwa v89, v72 dst_sel:DWORD dst_unused:UNUSED_PAD src0_sel:WORD_1
	v_cvt_pk_bf16_f32 v4, v4, v5
	v_cvt_pk_bf16_f32 v5, v82, v83
	global_store_dwordx2 v[76:77], v[4:5], off offset:3072
	v_mul_f32_e32 v4, v74, v98
	v_mul_f32_e32 v5, v75, v98
	v_mul_f32_e32 v74, v78, v98
	v_mul_f32_e32 v75, v79, v98
	ds_read_b128 v[78:81], v99 offset:7168
	ds_read_b128 v[82:85], v99 offset:48128
	v_cvt_f32_f16_e32 v88, v72
	s_waitcnt vmcnt(61)
	v_cvt_f32_f16_sdwa v87, v71 dst_sel:DWORD dst_unused:UNUSED_PAD src0_sel:WORD_1
	v_cvt_f32_f16_e32 v86, v71
	v_mov_b32_e32 v72, v91
	s_waitcnt lgkmcnt(0)
	v_fma_f32 v74, v74, v80, v84
	v_fma_f32 v75, v75, v81, v85
	v_cvt_f32_f16_sdwa v85, v70 dst_sel:DWORD dst_unused:UNUSED_PAD src0_sel:WORD_1
	v_cvt_f32_f16_e32 v84, v70
	v_fma_f32 v4, v4, v78, v82
	v_fma_f32 v5, v5, v79, v83
	v_mov_b32_e32 v70, v89
	v_cvt_pk_bf16_f32 v4, v4, v5
	v_cvt_pk_bf16_f32 v5, v74, v75
	global_store_dwordx2 v[76:77], v[4:5], off offset:3584
	v_mov_b32_e32 v71, v85
	s_waitcnt vmcnt(61)
	v_cvt_f32_f16_sdwa v75, v68 dst_sel:DWORD dst_unused:UNUSED_PAD src0_sel:WORD_1
	v_cvt_f32_f16_sdwa v77, v69 dst_sel:DWORD dst_unused:UNUSED_PAD src0_sel:WORD_1
	v_mov_b32_e32 v4, v88
	v_mov_b32_e32 v5, v84
	v_mul_f32_e32 v70, v70, v70
	v_mul_f32_e32 v71, v71, v71
	v_mov_b32_e32 v73, v87
	v_cvt_f32_f16_e32 v74, v68
	v_cvt_f32_f16_e32 v76, v69
	s_waitcnt vmcnt(60)
	v_cvt_f32_f16_sdwa v79, v66 dst_sel:DWORD dst_unused:UNUSED_PAD src0_sel:WORD_1
	v_fma_f32 v4, v4, v4, v70
	v_fma_f32 v5, v5, v5, v71
	v_mov_b32_e32 v70, v90
	v_mov_b32_e32 v71, v86
	v_mul_f32_e32 v72, v72, v72
	v_mul_f32_e32 v73, v73, v73
	v_cvt_f32_f16_e32 v78, v66
	v_cvt_f32_f16_sdwa v81, v67 dst_sel:DWORD dst_unused:UNUSED_PAD src0_sel:WORD_1
	v_fma_f32 v70, v70, v70, v72
	v_fma_f32 v71, v71, v71, v73
	v_cvt_f32_f16_e32 v80, v67
	v_add_f32_e32 v4, v4, v70
	v_add_f32_e32 v5, v5, v71
	v_mov_b32_e32 v70, v75
	v_mov_b32_e32 v71, v77
	v_mov_b32_e32 v68, v74
	v_mov_b32_e32 v69, v76
	v_mul_f32_e32 v70, v70, v70
	v_mul_f32_e32 v71, v71, v71
	v_mul_f32_e32 v66, v79, v79
	v_fma_f32 v68, v68, v68, v70
	v_fma_f32 v69, v69, v69, v71
	v_fma_f32 v72, v78, v78, v66
	v_fma_f32 v73, v79, v79, v66
	v_mul_f32_e32 v66, v81, v81
	v_add_f32_e32 v70, v68, v69
	v_add_f32_e32 v71, v69, v68
	v_fma_f32 v82, v80, v80, v66
	v_fma_f32 v83, v81, v81, v66
	s_waitcnt vmcnt(59)
	v_cvt_f32_f16_sdwa v67, v64 dst_sel:DWORD dst_unused:UNUSED_PAD src0_sel:WORD_1
	v_cvt_f32_f16_e32 v66, v64
	v_cvt_f32_f16_sdwa v69, v65 dst_sel:DWORD dst_unused:UNUSED_PAD src0_sel:WORD_1
	v_cvt_f32_f16_e32 v68, v65
	v_pk_add_f32 v[4:5], v[4:5], v[4:5] op_sel:[0,1] op_sel_hi:[1,0]
	v_mul_f32_e32 v64, v66, v66
	v_mul_f32_e32 v65, v67, v67
	v_mul_f32_e32 v92, v68, v68
	v_mul_f32_e32 v93, v69, v69
	v_mov_b32_e32 v5, v64
	v_mov_b32_e32 v71, v65
	v_mov_b32_e32 v73, v92
	v_mov_b32_e32 v83, v93
	v_add_f32_e32 v4, v4, v70
	v_add_f32_e32 v5, v5, v71
	v_add_f32_e32 v64, v72, v82
	v_add_f32_e32 v65, v73, v83
	s_waitcnt vmcnt(58)
	v_cvt_f32_f16_sdwa v71, v62 dst_sel:DWORD dst_unused:UNUSED_PAD src0_sel:WORD_1
	v_cvt_f32_f16_sdwa v73, v63 dst_sel:DWORD dst_unused:UNUSED_PAD src0_sel:WORD_1
	v_cvt_f32_f16_e32 v70, v62
	v_cvt_f32_f16_e32 v72, v63
	v_add_f32_e32 v4, v4, v64
	v_add_f32_e32 v5, v5, v65
	v_mov_b32_e32 v62, v71
	v_mov_b32_e32 v63, v73
	v_add_f32_e32 v82, v4, v5
	v_add_f32_e32 v83, v5, v4
	v_mov_b32_e32 v4, v70
	v_mov_b32_e32 v5, v72
	v_mul_f32_e32 v62, v62, v62
	v_mul_f32_e32 v63, v63, v63
	s_waitcnt vmcnt(56)
	v_cvt_f32_f16_sdwa v65, v59 dst_sel:DWORD dst_unused:UNUSED_PAD src0_sel:WORD_1
	v_fma_f32 v4, v4, v4, v62
	v_fma_f32 v5, v5, v5, v63
	v_cvt_f32_f16_sdwa v63, v61 dst_sel:DWORD dst_unused:UNUSED_PAD src0_sel:WORD_1
	v_add_f32_e32 v92, v4, v5
	v_add_f32_e32 v93, v5, v4
	v_cvt_f32_f16_sdwa v5, v60 dst_sel:DWORD dst_unused:UNUSED_PAD src0_sel:WORD_1
	v_cvt_f32_f16_e32 v4, v60
	v_cvt_f32_f16_e32 v62, v61
	v_cvt_f32_f16_e32 v64, v59
	v_mul_f32_e32 v60, v5, v5
	v_fma_f32 v94, v4, v4, v60
	v_fma_f32 v95, v5, v5, v60
	v_mul_f32_e32 v60, v63, v63
	v_fma_f32 v96, v62, v62, v60
	v_fma_f32 v97, v63, v63, v60
	v_cvt_f32_f16_sdwa v61, v58 dst_sel:DWORD dst_unused:UNUSED_PAD src0_sel:WORD_1
	v_cvt_f32_f16_e32 v60, v58
	v_mul_f32_e32 v98, v64, v64
	v_mul_f32_e32 v99, v65, v65
	v_mul_f32_e32 v58, v60, v60
	v_mul_f32_e32 v59, v61, v61
	s_nop 0
	v_mov_b32_e32 v83, v58
	v_mov_b32_e32 v93, v59
	v_mov_b32_e32 v95, v98
	v_mov_b32_e32 v97, v99
	v_add_f32_e32 v58, v82, v92
	v_add_f32_e32 v59, v83, v93
	v_add_f32_e32 v82, v94, v96
	v_add_f32_e32 v83, v95, v97
	s_nop 0
	v_add_f32_e32 v58, v58, v82
	v_add_f32_e32 v59, v59, v83
	s_nop 0
	v_add_f32_e32 v58, v58, v59
	s_nop 1
	v_add_f32_dpp v58, v58, v58 quad_perm:[1,0,3,2] row_mask:0xf bank_mask:0xf bound_ctrl:1
	s_nop 1
	v_add_f32_dpp v58, v58, v58 quad_perm:[2,3,0,1] row_mask:0xf bank_mask:0xf bound_ctrl:1
	s_nop 1
	v_add_f32_dpp v58, v58, v58 row_half_mirror row_mask:0xf bank_mask:0xf bound_ctrl:1
	s_nop 1
	v_add_f32_dpp v58, v58, v58 row_mirror row_mask:0xf bank_mask:0xf bound_ctrl:1
	s_nop 0
	v_readlane_b32 s5, v58, 16
	v_readlane_b32 s11, v58, 48
	v_readlane_b32 s6, v58, 0
	v_readlane_b32 s7, v58, 32
	v_mov_b32_e32 v58, s5
	v_mov_b32_e32 v59, s11
	v_add_f32_e32 v58, s6, v58
	v_add_f32_e32 v59, s7, v59
	s_lshl_b32 s5, s22, 1
	v_add_f32_e32 v58, v58, v59
	v_fmamk_f32 v58, v58, 0x3a000000, v252
	v_cmp_gt_f32_e32 vcc, s55, v58
	v_mul_f32_e32 v59, 0x4f800000, v58
	s_and_b32 s5, s5, 0xffffe000
	v_cndmask_b32_e32 v58, v58, v59, vcc
	v_sqrt_f32_e32 v59, v58
	s_add_i32 s5, s5, 0
	v_add_u32_e32 v82, -1, v59
	v_fma_f32 v83, -v82, v59, v58
	v_cmp_ge_f32_e64 s[6:7], 0, v83
	v_add_u32_e32 v83, 1, v59
	s_nop 0
	v_cndmask_b32_e64 v82, v59, v82, s[6:7]
	v_fma_f32 v59, -v83, v59, v58
	v_cmp_lt_f32_e64 s[6:7], 0, v59
	s_nop 1
	v_cndmask_b32_e64 v59, v82, v83, s[6:7]
	v_mul_f32_e32 v82, 0x37800000, v59
	v_cndmask_b32_e32 v59, v59, v82, vcc
	v_cmp_class_f32_e32 vcc, v58, v253
	s_nop 1
	v_cndmask_b32_e32 v58, v59, v58, vcc
	v_div_scale_f32 v59, s[6:7], v58, v58, 1.0
	v_rcp_f32_e32 v82, v59
	s_nop 0
	v_fma_f32 v83, -v59, v82, 1.0
	v_fmac_f32_e32 v82, v83, v82
	v_div_scale_f32 v83, vcc, 1.0, v58, 1.0
	v_mul_f32_e32 v92, v83, v82
	v_fma_f32 v93, -v59, v92, v83
	v_fmac_f32_e32 v92, v93, v82
	v_fma_f32 v59, -v59, v92, v83
	v_div_fmas_f32 v59, v59, v82, v92
	v_div_fixup_f32 v82, v59, v58, 1.0
	v_mul_f32_e32 v96, v88, v82
	v_mul_f32_e32 v97, v89, v82
	v_mul_f32_e32 v98, v90, v82
	v_mul_f32_e32 v99, v91, v82
	v_add_u32_e32 v83, s5, v0
	ds_read_b128 v[88:91], v83
	ds_read_b128 v[92:95], v83 offset:40960
	v_lshl_add_u64 v[58:59], s[24:25], 1, v[2:3]
	v_lshl_add_u64 v[58:59], v[58:59], 0, v[6:7]
	v_mul_f32_e32 v4, v4, v82
	v_mul_f32_e32 v5, v5, v82
	v_mul_f32_e32 v62, v62, v82
	v_mul_f32_e32 v63, v63, v82
	s_waitcnt lgkmcnt(0)
	v_fma_f32 v90, v90, v98, v94
	v_fma_f32 v91, v91, v99, v95
	v_fma_f32 v88, v88, v96, v92
	v_fma_f32 v89, v89, v97, v93
	v_mul_f32_e32 v92, v84, v82
	v_mul_f32_e32 v93, v85, v82
	v_cvt_pk_bf16_f32 v88, v88, v89
	v_cvt_pk_bf16_f32 v89, v90, v91
	global_store_dwordx2 v[58:59], v[88:89], off
	v_mul_f32_e32 v94, v86, v82
	v_mul_f32_e32 v95, v87, v82
	ds_read_b128 v[84:87], v83 offset:1024
	ds_read_b128 v[88:91], v83 offset:41984
	s_waitcnt lgkmcnt(0)
	v_fma_f32 v86, v86, v94, v90
	v_fma_f32 v87, v87, v95, v91
	v_fma_f32 v84, v84, v92, v88
	v_fma_f32 v85, v85, v93, v89
	v_mul_f32_e32 v88, v74, v82
	v_mul_f32_e32 v89, v75, v82
	v_cvt_pk_bf16_f32 v84, v84, v85
	v_cvt_pk_bf16_f32 v85, v86, v87
	global_store_dwordx2 v[58:59], v[84:85], off offset:512
	v_mul_f32_e32 v90, v76, v82
	v_mul_f32_e32 v91, v77, v82
	ds_read_b128 v[74:77], v83 offset:2048
	ds_read_b128 v[84:87], v83 offset:43008
	s_waitcnt lgkmcnt(0)
	v_fma_f32 v76, v76, v90, v86
	v_fma_f32 v77, v77, v91, v87
	v_fma_f32 v74, v74, v88, v84
	v_fma_f32 v75, v75, v89, v85
	v_mul_f32_e32 v84, v78, v82
	v_mul_f32_e32 v85, v79, v82
	v_cvt_pk_bf16_f32 v74, v74, v75
	v_cvt_pk_bf16_f32 v75, v76, v77
	global_store_dwordx2 v[58:59], v[74:75], off offset:1024
	v_mul_f32_e32 v86, v80, v82
	v_mul_f32_e32 v87, v81, v82
	ds_read_b128 v[74:77], v83 offset:3072
	ds_read_b128 v[78:81], v83 offset:44032
	s_waitcnt lgkmcnt(0)
	v_fma_f32 v76, v86, v76, v80
	v_fma_f32 v77, v87, v77, v81
	v_fma_f32 v74, v84, v74, v78
	v_fma_f32 v75, v85, v75, v79
	v_mul_f32_e32 v78, v66, v82
	v_mul_f32_e32 v79, v67, v82
	v_cvt_pk_bf16_f32 v74, v74, v75
	v_cvt_pk_bf16_f32 v75, v76, v77
	global_store_dwordx2 v[58:59], v[74:75], off offset:1536
	v_mul_f32_e32 v80, v68, v82
	v_mul_f32_e32 v81, v69, v82
	ds_read_b128 v[66:69], v83 offset:4096
	ds_read_b128 v[74:77], v83 offset:45056
	s_waitcnt lgkmcnt(0)
	v_fma_f32 v68, v80, v68, v76
	v_fma_f32 v69, v81, v69, v77
	v_fma_f32 v66, v78, v66, v74
	v_fma_f32 v67, v79, v67, v75
	v_mul_f32_e32 v74, v70, v82
	v_mul_f32_e32 v75, v71, v82
	v_cvt_pk_bf16_f32 v66, v66, v67
	v_cvt_pk_bf16_f32 v67, v68, v69
	global_store_dwordx2 v[58:59], v[66:67], off offset:2048
	v_mul_f32_e32 v76, v72, v82
	v_mul_f32_e32 v77, v73, v82
	ds_read_b128 v[66:69], v83 offset:5120
	ds_read_b128 v[70:73], v83 offset:46080
	s_waitcnt lgkmcnt(0)
	v_fma_f32 v68, v76, v68, v72
	v_fma_f32 v69, v77, v69, v73
	v_fma_f32 v66, v74, v66, v70
	v_fma_f32 v67, v75, v67, v71
	s_waitcnt vmcnt(60)
	v_cvt_f32_f16_sdwa v75, v57 dst_sel:DWORD dst_unused:UNUSED_PAD src0_sel:WORD_1
	v_cvt_pk_bf16_f32 v66, v66, v67
	v_cvt_pk_bf16_f32 v67, v68, v69
	global_store_dwordx2 v[58:59], v[66:67], off offset:2560
	ds_read_b128 v[66:69], v83 offset:6144
	ds_read_b128 v[70:73], v83 offset:47104
	v_cvt_f32_f16_e32 v74, v57
	s_waitcnt lgkmcnt(0)
	v_fma_f32 v62, v62, v68, v72
	v_fma_f32 v63, v63, v69, v73
	v_fma_f32 v4, v4, v66, v70
	v_fma_f32 v5, v5, v67, v71
	v_mul_f32_e32 v68, v64, v82
	v_mul_f32_e32 v69, v65, v82
	v_cvt_pk_bf16_f32 v4, v4, v5
	v_cvt_pk_bf16_f32 v5, v62, v63
	global_store_dwordx2 v[58:59], v[4:5], off offset:3072
	v_mul_f32_e32 v4, v60, v82
	v_mul_f32_e32 v5, v61, v82
	ds_read_b128 v[60:63], v83 offset:7168
	ds_read_b128 v[64:67], v83 offset:48128
	v_cvt_f32_f16_sdwa v73, v56 dst_sel:DWORD dst_unused:UNUSED_PAD src0_sel:WORD_1
	v_cvt_f32_f16_e32 v72, v56
	s_waitcnt vmcnt(61)
	v_cvt_f32_f16_sdwa v71, v55 dst_sel:DWORD dst_unused:UNUSED_PAD src0_sel:WORD_1
	v_cvt_f32_f16_e32 v70, v55
	s_waitcnt lgkmcnt(0)
	v_fma_f32 v62, v68, v62, v66
	v_fma_f32 v63, v69, v63, v67
	v_cvt_f32_f16_sdwa v69, v54 dst_sel:DWORD dst_unused:UNUSED_PAD src0_sel:WORD_1
	v_cvt_f32_f16_e32 v68, v54
	v_fma_f32 v4, v4, v60, v64
	v_fma_f32 v5, v5, v61, v65
	v_mov_b32_e32 v54, v73
	v_cvt_pk_bf16_f32 v4, v4, v5
	v_cvt_pk_bf16_f32 v5, v62, v63
	global_store_dwordx2 v[58:59], v[4:5], off offset:3584
	v_mov_b32_e32 v55, v69
	s_waitcnt vmcnt(61)
	v_cvt_f32_f16_sdwa v59, v52 dst_sel:DWORD dst_unused:UNUSED_PAD src0_sel:WORD_1
	v_cvt_f32_f16_sdwa v61, v53 dst_sel:DWORD dst_unused:UNUSED_PAD src0_sel:WORD_1
	v_mov_b32_e32 v4, v72
	v_mov_b32_e32 v5, v68
	v_mul_f32_e32 v54, v54, v54
	v_mul_f32_e32 v55, v55, v55
	v_mov_b32_e32 v56, v75
	v_mov_b32_e32 v57, v71
	v_cvt_f32_f16_e32 v58, v52
	v_cvt_f32_f16_e32 v60, v53
	s_waitcnt vmcnt(60)
	v_cvt_f32_f16_sdwa v63, v50 dst_sel:DWORD dst_unused:UNUSED_PAD src0_sel:WORD_1
	v_fma_f32 v4, v4, v4, v54
	v_fma_f32 v5, v5, v5, v55
	v_mov_b32_e32 v54, v74
	v_mov_b32_e32 v55, v70
	v_mul_f32_e32 v56, v56, v56
	v_mul_f32_e32 v57, v57, v57
	v_cvt_f32_f16_e32 v62, v50
	v_cvt_f32_f16_sdwa v65, v51 dst_sel:DWORD dst_unused:UNUSED_PAD src0_sel:WORD_1
	v_fma_f32 v54, v54, v54, v56
	v_fma_f32 v55, v55, v55, v57
	v_cvt_f32_f16_e32 v64, v51
	v_add_f32_e32 v4, v4, v54
	v_add_f32_e32 v5, v5, v55
	v_mov_b32_e32 v54, v59
	v_mov_b32_e32 v55, v61
	v_mov_b32_e32 v52, v58
	v_mov_b32_e32 v53, v60
	v_mul_f32_e32 v54, v54, v54
	v_mul_f32_e32 v55, v55, v55
	v_mul_f32_e32 v50, v63, v63
	v_fma_f32 v52, v52, v52, v54
	v_fma_f32 v53, v53, v53, v55
	v_fma_f32 v56, v62, v62, v50
	v_fma_f32 v57, v63, v63, v50
	v_mul_f32_e32 v50, v65, v65
	v_add_f32_e32 v54, v52, v53
	v_add_f32_e32 v55, v53, v52
	v_fma_f32 v66, v64, v64, v50
	v_fma_f32 v67, v65, v65, v50
	s_waitcnt vmcnt(59)
	v_cvt_f32_f16_sdwa v51, v48 dst_sel:DWORD dst_unused:UNUSED_PAD src0_sel:WORD_1
	v_cvt_f32_f16_e32 v50, v48
	v_cvt_f32_f16_sdwa v53, v49 dst_sel:DWORD dst_unused:UNUSED_PAD src0_sel:WORD_1
	v_cvt_f32_f16_e32 v52, v49
	v_pk_add_f32 v[4:5], v[4:5], v[4:5] op_sel:[0,1] op_sel_hi:[1,0]
	v_mul_f32_e32 v48, v50, v50
	v_mul_f32_e32 v49, v51, v51
	v_mul_f32_e32 v76, v52, v52
	v_mul_f32_e32 v77, v53, v53
	v_mov_b32_e32 v5, v48
	v_mov_b32_e32 v55, v49
	v_mov_b32_e32 v57, v76
	v_mov_b32_e32 v67, v77
	v_add_f32_e32 v4, v4, v54
	v_add_f32_e32 v5, v5, v55
	v_add_f32_e32 v48, v56, v66
	v_add_f32_e32 v49, v57, v67
	s_waitcnt vmcnt(58)
	v_cvt_f32_f16_sdwa v55, v46 dst_sel:DWORD dst_unused:UNUSED_PAD src0_sel:WORD_1
	v_cvt_f32_f16_sdwa v57, v47 dst_sel:DWORD dst_unused:UNUSED_PAD src0_sel:WORD_1
	v_cvt_f32_f16_e32 v54, v46
	v_cvt_f32_f16_e32 v56, v47
	v_add_f32_e32 v4, v4, v48
	v_add_f32_e32 v5, v5, v49
	v_mov_b32_e32 v46, v55
	v_mov_b32_e32 v47, v57
	v_add_f32_e32 v66, v4, v5
	v_add_f32_e32 v67, v5, v4
	v_mov_b32_e32 v4, v54
	v_mov_b32_e32 v5, v56
	v_mul_f32_e32 v46, v46, v46
	v_mul_f32_e32 v47, v47, v47
	s_waitcnt vmcnt(56)
	v_cvt_f32_f16_sdwa v49, v43 dst_sel:DWORD dst_unused:UNUSED_PAD src0_sel:WORD_1
	v_fma_f32 v4, v4, v4, v46
	v_fma_f32 v5, v5, v5, v47
	v_cvt_f32_f16_sdwa v47, v45 dst_sel:DWORD dst_unused:UNUSED_PAD src0_sel:WORD_1
	v_add_f32_e32 v76, v4, v5
	v_add_f32_e32 v77, v5, v4
	v_cvt_f32_f16_sdwa v5, v44 dst_sel:DWORD dst_unused:UNUSED_PAD src0_sel:WORD_1
	v_cvt_f32_f16_e32 v4, v44
	v_cvt_f32_f16_e32 v46, v45
	v_cvt_f32_f16_e32 v48, v43
	v_mul_f32_e32 v44, v5, v5
	v_fma_f32 v78, v4, v4, v44
	v_fma_f32 v79, v5, v5, v44
	v_mul_f32_e32 v44, v47, v47
	v_fma_f32 v80, v46, v46, v44
	v_fma_f32 v81, v47, v47, v44
	v_cvt_f32_f16_sdwa v45, v42 dst_sel:DWORD dst_unused:UNUSED_PAD src0_sel:WORD_1
	v_cvt_f32_f16_e32 v44, v42
	v_mul_f32_e32 v82, v48, v48
	v_mul_f32_e32 v83, v49, v49
	v_mul_f32_e32 v42, v44, v44
	v_mul_f32_e32 v43, v45, v45
	s_nop 0
	v_mov_b32_e32 v67, v42
	v_mov_b32_e32 v77, v43
	v_mov_b32_e32 v79, v82
	v_mov_b32_e32 v81, v83
	v_add_f32_e32 v42, v66, v76
	v_add_f32_e32 v43, v67, v77
	v_add_f32_e32 v66, v78, v80
	v_add_f32_e32 v67, v79, v81
	s_nop 0
	v_add_f32_e32 v42, v42, v66
	v_add_f32_e32 v43, v43, v67
	s_nop 0
	v_add_f32_e32 v42, v42, v43
	s_nop 1
	v_add_f32_dpp v42, v42, v42 quad_perm:[1,0,3,2] row_mask:0xf bank_mask:0xf bound_ctrl:1
	s_nop 1
	v_add_f32_dpp v42, v42, v42 quad_perm:[2,3,0,1] row_mask:0xf bank_mask:0xf bound_ctrl:1
	s_nop 1
	v_add_f32_dpp v42, v42, v42 row_half_mirror row_mask:0xf bank_mask:0xf bound_ctrl:1
	s_nop 1
	v_add_f32_dpp v42, v42, v42 row_mirror row_mask:0xf bank_mask:0xf bound_ctrl:1
	s_nop 0
	v_readlane_b32 s5, v42, 16
	v_readlane_b32 s11, v42, 48
	v_readlane_b32 s6, v42, 0
	v_readlane_b32 s7, v42, 32
	v_mov_b32_e32 v42, s5
	v_mov_b32_e32 v43, s11
	v_add_f32_e32 v42, s6, v42
	v_add_f32_e32 v43, s7, v43
	s_lshl_b32 s5, s18, 1
	v_add_f32_e32 v42, v42, v43
	v_fmamk_f32 v42, v42, 0x3a000000, v252
	v_cmp_gt_f32_e32 vcc, s55, v42
	v_mul_f32_e32 v43, 0x4f800000, v42
	s_and_b32 s5, s5, 0xffffe000
	v_cndmask_b32_e32 v42, v42, v43, vcc
	v_sqrt_f32_e32 v43, v42
	s_add_i32 s5, s5, 0
	v_add_u32_e32 v66, -1, v43
	v_fma_f32 v67, -v66, v43, v42
	v_cmp_ge_f32_e64 s[6:7], 0, v67
	v_add_u32_e32 v67, 1, v43
	s_nop 0
	v_cndmask_b32_e64 v66, v43, v66, s[6:7]
	v_fma_f32 v43, -v67, v43, v42
	v_cmp_lt_f32_e64 s[6:7], 0, v43
	s_nop 1
	v_cndmask_b32_e64 v43, v66, v67, s[6:7]
	v_mul_f32_e32 v66, 0x37800000, v43
	v_cndmask_b32_e32 v43, v43, v66, vcc
	v_cmp_class_f32_e32 vcc, v42, v253
	s_nop 1
	v_cndmask_b32_e32 v42, v43, v42, vcc
	v_div_scale_f32 v43, s[6:7], v42, v42, 1.0
	v_rcp_f32_e32 v66, v43
	s_nop 0
	v_fma_f32 v67, -v43, v66, 1.0
	v_fmac_f32_e32 v66, v67, v66
	v_div_scale_f32 v67, vcc, 1.0, v42, 1.0
	v_mul_f32_e32 v76, v67, v66
	v_fma_f32 v77, -v43, v76, v67
	v_fmac_f32_e32 v76, v77, v66
	v_fma_f32 v43, -v43, v76, v67
	v_div_fmas_f32 v43, v43, v66, v76
	v_div_fixup_f32 v66, v43, v42, 1.0
	v_mul_f32_e32 v80, v72, v66
	v_mul_f32_e32 v81, v73, v66
	v_mul_f32_e32 v82, v74, v66
	v_mul_f32_e32 v83, v75, v66
	v_add_u32_e32 v67, s5, v0
	ds_read_b128 v[72:75], v67
	ds_read_b128 v[76:79], v67 offset:40960
	v_lshl_add_u64 v[42:43], s[20:21], 1, v[2:3]
	v_lshl_add_u64 v[42:43], v[42:43], 0, v[6:7]
	v_mul_f32_e32 v4, v4, v66
	v_mul_f32_e32 v5, v5, v66
	v_mul_f32_e32 v46, v46, v66
	v_mul_f32_e32 v47, v47, v66
	s_waitcnt lgkmcnt(0)
	v_fma_f32 v74, v74, v82, v78
	v_fma_f32 v75, v75, v83, v79
	v_fma_f32 v72, v72, v80, v76
	v_fma_f32 v73, v73, v81, v77
	v_mul_f32_e32 v76, v68, v66
	v_mul_f32_e32 v77, v69, v66
	v_cvt_pk_bf16_f32 v72, v72, v73
	v_cvt_pk_bf16_f32 v73, v74, v75
	global_store_dwordx2 v[42:43], v[72:73], off
	v_mul_f32_e32 v78, v70, v66
	v_mul_f32_e32 v79, v71, v66
	ds_read_b128 v[68:71], v67 offset:1024
	ds_read_b128 v[72:75], v67 offset:41984
	s_waitcnt lgkmcnt(0)
	v_fma_f32 v70, v70, v78, v74
	v_fma_f32 v71, v71, v79, v75
	v_fma_f32 v68, v68, v76, v72
	v_fma_f32 v69, v69, v77, v73
	v_mul_f32_e32 v72, v58, v66
	v_mul_f32_e32 v73, v59, v66
	v_cvt_pk_bf16_f32 v68, v68, v69
	v_cvt_pk_bf16_f32 v69, v70, v71
	global_store_dwordx2 v[42:43], v[68:69], off offset:512
	v_mul_f32_e32 v74, v60, v66
	v_mul_f32_e32 v75, v61, v66
	ds_read_b128 v[58:61], v67 offset:2048
	ds_read_b128 v[68:71], v67 offset:43008
	s_waitcnt lgkmcnt(0)
	v_fma_f32 v60, v60, v74, v70
	v_fma_f32 v61, v61, v75, v71
	v_fma_f32 v58, v58, v72, v68
	v_fma_f32 v59, v59, v73, v69
	v_mul_f32_e32 v68, v62, v66
	v_mul_f32_e32 v69, v63, v66
	v_cvt_pk_bf16_f32 v58, v58, v59
	v_cvt_pk_bf16_f32 v59, v60, v61
	global_store_dwordx2 v[42:43], v[58:59], off offset:1024
	v_mul_f32_e32 v70, v64, v66
	v_mul_f32_e32 v71, v65, v66
	ds_read_b128 v[58:61], v67 offset:3072
	ds_read_b128 v[62:65], v67 offset:44032
	s_waitcnt lgkmcnt(0)
	v_fma_f32 v60, v70, v60, v64
	v_fma_f32 v61, v71, v61, v65
	v_fma_f32 v58, v68, v58, v62
	v_fma_f32 v59, v69, v59, v63
	v_mul_f32_e32 v62, v50, v66
	v_mul_f32_e32 v63, v51, v66
	v_cvt_pk_bf16_f32 v58, v58, v59
	v_cvt_pk_bf16_f32 v59, v60, v61
	global_store_dwordx2 v[42:43], v[58:59], off offset:1536
	v_mul_f32_e32 v64, v52, v66
	v_mul_f32_e32 v65, v53, v66
	ds_read_b128 v[50:53], v67 offset:4096
	ds_read_b128 v[58:61], v67 offset:45056
	s_waitcnt lgkmcnt(0)
	v_fma_f32 v52, v64, v52, v60
	v_fma_f32 v53, v65, v53, v61
	v_fma_f32 v50, v62, v50, v58
	v_fma_f32 v51, v63, v51, v59
	v_mul_f32_e32 v58, v54, v66
	v_mul_f32_e32 v59, v55, v66
	v_cvt_pk_bf16_f32 v50, v50, v51
	v_cvt_pk_bf16_f32 v51, v52, v53
	global_store_dwordx2 v[42:43], v[50:51], off offset:2048
	v_mul_f32_e32 v60, v56, v66
	v_mul_f32_e32 v61, v57, v66
	ds_read_b128 v[50:53], v67 offset:5120
	ds_read_b128 v[54:57], v67 offset:46080
	s_waitcnt lgkmcnt(0)
	v_fma_f32 v52, v60, v52, v56
	v_fma_f32 v53, v61, v53, v57
	v_fma_f32 v50, v58, v50, v54
	v_fma_f32 v51, v59, v51, v55
	s_waitcnt vmcnt(60)
	v_cvt_f32_f16_sdwa v59, v41 dst_sel:DWORD dst_unused:UNUSED_PAD src0_sel:WORD_1
	v_cvt_pk_bf16_f32 v50, v50, v51
	v_cvt_pk_bf16_f32 v51, v52, v53
	global_store_dwordx2 v[42:43], v[50:51], off offset:2560
	ds_read_b128 v[50:53], v67 offset:6144
	ds_read_b128 v[54:57], v67 offset:47104
	v_cvt_f32_f16_e32 v58, v41
	s_waitcnt lgkmcnt(0)
	v_fma_f32 v46, v46, v52, v56
	v_fma_f32 v47, v47, v53, v57
	v_fma_f32 v4, v4, v50, v54
	v_fma_f32 v5, v5, v51, v55
	v_mul_f32_e32 v52, v48, v66
	v_mul_f32_e32 v53, v49, v66
	v_cvt_pk_bf16_f32 v4, v4, v5
	v_cvt_pk_bf16_f32 v5, v46, v47
	global_store_dwordx2 v[42:43], v[4:5], off offset:3072
	v_mul_f32_e32 v4, v44, v66
	v_mul_f32_e32 v5, v45, v66
	ds_read_b128 v[44:47], v67 offset:7168
	ds_read_b128 v[48:51], v67 offset:48128
	v_cvt_f32_f16_sdwa v57, v40 dst_sel:DWORD dst_unused:UNUSED_PAD src0_sel:WORD_1
	v_cvt_f32_f16_e32 v56, v40
	s_waitcnt vmcnt(61)
	v_cvt_f32_f16_sdwa v55, v39 dst_sel:DWORD dst_unused:UNUSED_PAD src0_sel:WORD_1
	v_cvt_f32_f16_e32 v54, v39
	s_waitcnt lgkmcnt(0)
	v_fma_f32 v46, v52, v46, v50
	v_fma_f32 v47, v53, v47, v51
	v_cvt_f32_f16_sdwa v53, v38 dst_sel:DWORD dst_unused:UNUSED_PAD src0_sel:WORD_1
	v_cvt_f32_f16_e32 v52, v38
	v_fma_f32 v4, v4, v44, v48
	v_fma_f32 v5, v5, v45, v49
	v_mov_b32_e32 v38, v57
	v_cvt_pk_bf16_f32 v4, v4, v5
	v_cvt_pk_bf16_f32 v5, v46, v47
	global_store_dwordx2 v[42:43], v[4:5], off offset:3584
	v_mov_b32_e32 v39, v53
	s_waitcnt vmcnt(61)
	v_cvt_f32_f16_sdwa v43, v36 dst_sel:DWORD dst_unused:UNUSED_PAD src0_sel:WORD_1
	v_cvt_f32_f16_sdwa v45, v37 dst_sel:DWORD dst_unused:UNUSED_PAD src0_sel:WORD_1
	v_mov_b32_e32 v4, v56
	v_mov_b32_e32 v5, v52
	v_mul_f32_e32 v38, v38, v38
	v_mul_f32_e32 v39, v39, v39
	v_mov_b32_e32 v40, v59
	v_mov_b32_e32 v41, v55
	v_cvt_f32_f16_e32 v42, v36
	v_cvt_f32_f16_e32 v44, v37
	s_waitcnt vmcnt(60)
	v_cvt_f32_f16_sdwa v47, v34 dst_sel:DWORD dst_unused:UNUSED_PAD src0_sel:WORD_1
	v_fma_f32 v4, v4, v4, v38
	v_fma_f32 v5, v5, v5, v39
	v_mov_b32_e32 v38, v58
	v_mov_b32_e32 v39, v54
	v_mul_f32_e32 v40, v40, v40
	v_mul_f32_e32 v41, v41, v41
	v_cvt_f32_f16_e32 v46, v34
	v_cvt_f32_f16_sdwa v49, v35 dst_sel:DWORD dst_unused:UNUSED_PAD src0_sel:WORD_1
	v_fma_f32 v38, v38, v38, v40
	v_fma_f32 v39, v39, v39, v41
	v_cvt_f32_f16_e32 v48, v35
	v_add_f32_e32 v4, v4, v38
	v_add_f32_e32 v5, v5, v39
	v_mov_b32_e32 v38, v43
	v_mov_b32_e32 v39, v45
	v_mov_b32_e32 v36, v42
	v_mov_b32_e32 v37, v44
	v_mul_f32_e32 v38, v38, v38
	v_mul_f32_e32 v39, v39, v39
	v_mul_f32_e32 v34, v47, v47
	v_fma_f32 v36, v36, v36, v38
	v_fma_f32 v37, v37, v37, v39
	v_fma_f32 v40, v46, v46, v34
	v_fma_f32 v41, v47, v47, v34
	v_mul_f32_e32 v34, v49, v49
	v_add_f32_e32 v38, v36, v37
	v_add_f32_e32 v39, v37, v36
	v_fma_f32 v50, v48, v48, v34
	v_fma_f32 v51, v49, v49, v34
	s_waitcnt vmcnt(59)
	v_cvt_f32_f16_sdwa v35, v32 dst_sel:DWORD dst_unused:UNUSED_PAD src0_sel:WORD_1
	v_cvt_f32_f16_e32 v34, v32
	v_cvt_f32_f16_sdwa v37, v33 dst_sel:DWORD dst_unused:UNUSED_PAD src0_sel:WORD_1
	v_cvt_f32_f16_e32 v36, v33
	v_pk_add_f32 v[4:5], v[4:5], v[4:5] op_sel:[0,1] op_sel_hi:[1,0]
	v_mul_f32_e32 v32, v34, v34
	v_mul_f32_e32 v33, v35, v35
	v_mul_f32_e32 v60, v36, v36
	v_mul_f32_e32 v61, v37, v37
	v_mov_b32_e32 v5, v32
	v_mov_b32_e32 v39, v33
	v_mov_b32_e32 v41, v60
	v_mov_b32_e32 v51, v61
	v_add_f32_e32 v4, v4, v38
	v_add_f32_e32 v5, v5, v39
	v_add_f32_e32 v32, v40, v50
	v_add_f32_e32 v33, v41, v51
	s_waitcnt vmcnt(58)
	v_cvt_f32_f16_sdwa v39, v30 dst_sel:DWORD dst_unused:UNUSED_PAD src0_sel:WORD_1
	v_cvt_f32_f16_sdwa v41, v31 dst_sel:DWORD dst_unused:UNUSED_PAD src0_sel:WORD_1
	v_cvt_f32_f16_e32 v38, v30
	v_cvt_f32_f16_e32 v40, v31
	v_add_f32_e32 v4, v4, v32
	v_add_f32_e32 v5, v5, v33
	v_mov_b32_e32 v30, v39
	v_mov_b32_e32 v31, v41
	v_add_f32_e32 v50, v4, v5
	v_add_f32_e32 v51, v5, v4
	v_mov_b32_e32 v4, v38
	v_mov_b32_e32 v5, v40
	v_mul_f32_e32 v30, v30, v30
	v_mul_f32_e32 v31, v31, v31
	s_waitcnt vmcnt(56)
	v_cvt_f32_f16_sdwa v33, v27 dst_sel:DWORD dst_unused:UNUSED_PAD src0_sel:WORD_1
	v_fma_f32 v4, v4, v4, v30
	v_fma_f32 v5, v5, v5, v31
	v_cvt_f32_f16_sdwa v31, v29 dst_sel:DWORD dst_unused:UNUSED_PAD src0_sel:WORD_1
	v_add_f32_e32 v60, v4, v5
	v_add_f32_e32 v61, v5, v4
	v_cvt_f32_f16_sdwa v5, v28 dst_sel:DWORD dst_unused:UNUSED_PAD src0_sel:WORD_1
	v_cvt_f32_f16_e32 v4, v28
	v_cvt_f32_f16_e32 v30, v29
	v_cvt_f32_f16_e32 v32, v27
	v_mul_f32_e32 v28, v5, v5
	v_fma_f32 v62, v4, v4, v28
	v_fma_f32 v63, v5, v5, v28
	v_mul_f32_e32 v28, v31, v31
	v_fma_f32 v64, v30, v30, v28
	v_fma_f32 v65, v31, v31, v28
	v_cvt_f32_f16_sdwa v29, v26 dst_sel:DWORD dst_unused:UNUSED_PAD src0_sel:WORD_1
	v_cvt_f32_f16_e32 v28, v26
	v_mul_f32_e32 v66, v32, v32
	v_mul_f32_e32 v67, v33, v33
	v_mul_f32_e32 v26, v28, v28
	v_mul_f32_e32 v27, v29, v29
	s_nop 0
	v_mov_b32_e32 v51, v26
	v_mov_b32_e32 v61, v27
	v_mov_b32_e32 v63, v66
	v_mov_b32_e32 v65, v67
	v_add_f32_e32 v26, v50, v60
	v_add_f32_e32 v27, v51, v61
	v_add_f32_e32 v50, v62, v64
	v_add_f32_e32 v51, v63, v65
	s_nop 0
	v_add_f32_e32 v26, v26, v50
	v_add_f32_e32 v27, v27, v51
	s_nop 0
	v_add_f32_e32 v26, v26, v27
	s_nop 1
	v_add_f32_dpp v26, v26, v26 quad_perm:[1,0,3,2] row_mask:0xf bank_mask:0xf bound_ctrl:1
	s_nop 1
	v_add_f32_dpp v26, v26, v26 quad_perm:[2,3,0,1] row_mask:0xf bank_mask:0xf bound_ctrl:1
	s_nop 1
	v_add_f32_dpp v26, v26, v26 row_half_mirror row_mask:0xf bank_mask:0xf bound_ctrl:1
	s_nop 1
	v_add_f32_dpp v26, v26, v26 row_mirror row_mask:0xf bank_mask:0xf bound_ctrl:1
	s_nop 0
	v_readlane_b32 s5, v26, 16
	v_readlane_b32 s11, v26, 48
	v_readlane_b32 s6, v26, 0
	v_readlane_b32 s7, v26, 32
	v_mov_b32_e32 v26, s5
	v_mov_b32_e32 v27, s11
	v_add_f32_e32 v26, s6, v26
	v_add_f32_e32 v27, s7, v27
	s_lshl_b32 s5, s14, 1
	v_add_f32_e32 v26, v26, v27
	v_fmamk_f32 v26, v26, 0x3a000000, v252
	v_cmp_gt_f32_e32 vcc, s55, v26
	v_mul_f32_e32 v27, 0x4f800000, v26
	s_and_b32 s5, s5, 0xffffe000
	v_cndmask_b32_e32 v26, v26, v27, vcc
	v_sqrt_f32_e32 v27, v26
	s_add_i32 s5, s5, 0
	v_add_u32_e32 v50, -1, v27
	v_fma_f32 v51, -v50, v27, v26
	v_cmp_ge_f32_e64 s[6:7], 0, v51
	v_add_u32_e32 v51, 1, v27
	s_nop 0
	v_cndmask_b32_e64 v50, v27, v50, s[6:7]
	v_fma_f32 v27, -v51, v27, v26
	v_cmp_lt_f32_e64 s[6:7], 0, v27
	s_nop 1
	v_cndmask_b32_e64 v27, v50, v51, s[6:7]
	v_mul_f32_e32 v50, 0x37800000, v27
	v_cndmask_b32_e32 v27, v27, v50, vcc
	v_cmp_class_f32_e32 vcc, v26, v253
	s_nop 1
	v_cndmask_b32_e32 v26, v27, v26, vcc
	v_div_scale_f32 v27, s[6:7], v26, v26, 1.0
	v_rcp_f32_e32 v50, v27
	s_nop 0
	v_fma_f32 v51, -v27, v50, 1.0
	v_fmac_f32_e32 v50, v51, v50
	v_div_scale_f32 v51, vcc, 1.0, v26, 1.0
	v_mul_f32_e32 v60, v51, v50
	v_fma_f32 v61, -v27, v60, v51
	v_fmac_f32_e32 v60, v61, v50
	v_fma_f32 v27, -v27, v60, v51
	v_div_fmas_f32 v27, v27, v50, v60
	v_div_fixup_f32 v50, v27, v26, 1.0
	v_mul_f32_e32 v64, v56, v50
	v_mul_f32_e32 v65, v57, v50
	v_mul_f32_e32 v66, v58, v50
	v_mul_f32_e32 v67, v59, v50
	v_add_u32_e32 v51, s5, v0
	ds_read_b128 v[56:59], v51
	ds_read_b128 v[60:63], v51 offset:40960
	v_lshl_add_u64 v[26:27], s[16:17], 1, v[2:3]
	v_lshl_add_u64 v[26:27], v[26:27], 0, v[6:7]
	v_mul_f32_e32 v4, v4, v50
	v_mul_f32_e32 v5, v5, v50
	v_mul_f32_e32 v30, v30, v50
	v_mul_f32_e32 v31, v31, v50
	s_waitcnt lgkmcnt(0)
	v_fma_f32 v58, v58, v66, v62
	v_fma_f32 v59, v59, v67, v63
	v_fma_f32 v56, v56, v64, v60
	v_fma_f32 v57, v57, v65, v61
	v_mul_f32_e32 v60, v52, v50
	v_mul_f32_e32 v61, v53, v50
	v_cvt_pk_bf16_f32 v56, v56, v57
	v_cvt_pk_bf16_f32 v57, v58, v59
	global_store_dwordx2 v[26:27], v[56:57], off
	v_mul_f32_e32 v62, v54, v50
	v_mul_f32_e32 v63, v55, v50
	ds_read_b128 v[52:55], v51 offset:1024
	ds_read_b128 v[56:59], v51 offset:41984
	s_waitcnt lgkmcnt(0)
	v_fma_f32 v54, v54, v62, v58
	v_fma_f32 v55, v55, v63, v59
	v_fma_f32 v52, v52, v60, v56
	v_fma_f32 v53, v53, v61, v57
	v_mul_f32_e32 v56, v42, v50
	v_mul_f32_e32 v57, v43, v50
	v_cvt_pk_bf16_f32 v52, v52, v53
	v_cvt_pk_bf16_f32 v53, v54, v55
	global_store_dwordx2 v[26:27], v[52:53], off offset:512
	v_mul_f32_e32 v58, v44, v50
	v_mul_f32_e32 v59, v45, v50
	ds_read_b128 v[42:45], v51 offset:2048
	ds_read_b128 v[52:55], v51 offset:43008
	s_waitcnt lgkmcnt(0)
	v_fma_f32 v44, v44, v58, v54
	v_fma_f32 v45, v45, v59, v55
	v_fma_f32 v42, v42, v56, v52
	v_fma_f32 v43, v43, v57, v53
	v_mul_f32_e32 v52, v46, v50
	v_mul_f32_e32 v53, v47, v50
	v_cvt_pk_bf16_f32 v42, v42, v43
	v_cvt_pk_bf16_f32 v43, v44, v45
	global_store_dwordx2 v[26:27], v[42:43], off offset:1024
	v_mul_f32_e32 v54, v48, v50
	v_mul_f32_e32 v55, v49, v50
	ds_read_b128 v[42:45], v51 offset:3072
	ds_read_b128 v[46:49], v51 offset:44032
	s_waitcnt lgkmcnt(0)
	v_fma_f32 v44, v54, v44, v48
	v_fma_f32 v45, v55, v45, v49
	v_fma_f32 v42, v52, v42, v46
	v_fma_f32 v43, v53, v43, v47
	v_mul_f32_e32 v46, v34, v50
	v_mul_f32_e32 v47, v35, v50
	v_cvt_pk_bf16_f32 v42, v42, v43
	v_cvt_pk_bf16_f32 v43, v44, v45
	global_store_dwordx2 v[26:27], v[42:43], off offset:1536
	v_mul_f32_e32 v48, v36, v50
	v_mul_f32_e32 v49, v37, v50
	ds_read_b128 v[34:37], v51 offset:4096
	ds_read_b128 v[42:45], v51 offset:45056
	s_waitcnt lgkmcnt(0)
	v_fma_f32 v36, v48, v36, v44
	v_fma_f32 v37, v49, v37, v45
	v_fma_f32 v34, v46, v34, v42
	v_fma_f32 v35, v47, v35, v43
	v_mul_f32_e32 v42, v38, v50
	v_mul_f32_e32 v43, v39, v50
	v_cvt_pk_bf16_f32 v34, v34, v35
	v_cvt_pk_bf16_f32 v35, v36, v37
	global_store_dwordx2 v[26:27], v[34:35], off offset:2048
	v_mul_f32_e32 v44, v40, v50
	v_mul_f32_e32 v45, v41, v50
	ds_read_b128 v[34:37], v51 offset:5120
	ds_read_b128 v[38:41], v51 offset:46080
	s_waitcnt lgkmcnt(0)
	v_fma_f32 v36, v44, v36, v40
	v_fma_f32 v37, v45, v37, v41
	v_fma_f32 v34, v42, v34, v38
	v_fma_f32 v35, v43, v35, v39
	s_waitcnt vmcnt(60)
	v_cvt_f32_f16_sdwa v43, v25 dst_sel:DWORD dst_unused:UNUSED_PAD src0_sel:WORD_1
	v_cvt_pk_bf16_f32 v34, v34, v35
	v_cvt_pk_bf16_f32 v35, v36, v37
	global_store_dwordx2 v[26:27], v[34:35], off offset:2560
	ds_read_b128 v[34:37], v51 offset:6144
	ds_read_b128 v[38:41], v51 offset:47104
	v_cvt_f32_f16_e32 v42, v25
	s_waitcnt lgkmcnt(0)
	v_fma_f32 v30, v30, v36, v40
	v_fma_f32 v31, v31, v37, v41
	v_fma_f32 v4, v4, v34, v38
	v_fma_f32 v5, v5, v35, v39
	v_mul_f32_e32 v36, v32, v50
	v_mul_f32_e32 v37, v33, v50
	v_cvt_pk_bf16_f32 v4, v4, v5
	v_cvt_pk_bf16_f32 v5, v30, v31
	global_store_dwordx2 v[26:27], v[4:5], off offset:3072
	v_mul_f32_e32 v4, v28, v50
	v_mul_f32_e32 v5, v29, v50
	ds_read_b128 v[28:31], v51 offset:7168
	ds_read_b128 v[32:35], v51 offset:48128
	v_cvt_f32_f16_sdwa v41, v24 dst_sel:DWORD dst_unused:UNUSED_PAD src0_sel:WORD_1
	v_cvt_f32_f16_e32 v40, v24
	s_waitcnt vmcnt(61)
	v_cvt_f32_f16_sdwa v39, v23 dst_sel:DWORD dst_unused:UNUSED_PAD src0_sel:WORD_1
	v_cvt_f32_f16_e32 v38, v23
	s_waitcnt lgkmcnt(0)
	v_fma_f32 v30, v36, v30, v34
	v_fma_f32 v31, v37, v31, v35
	v_cvt_f32_f16_sdwa v37, v22 dst_sel:DWORD dst_unused:UNUSED_PAD src0_sel:WORD_1
	v_cvt_f32_f16_e32 v36, v22
	v_fma_f32 v4, v4, v28, v32
	v_fma_f32 v5, v5, v29, v33
	v_mov_b32_e32 v22, v41
	v_cvt_pk_bf16_f32 v4, v4, v5
	v_cvt_pk_bf16_f32 v5, v30, v31
	global_store_dwordx2 v[26:27], v[4:5], off offset:3584
	v_mov_b32_e32 v23, v37
	s_waitcnt vmcnt(61)
	v_cvt_f32_f16_sdwa v27, v20 dst_sel:DWORD dst_unused:UNUSED_PAD src0_sel:WORD_1
	v_cvt_f32_f16_sdwa v29, v21 dst_sel:DWORD dst_unused:UNUSED_PAD src0_sel:WORD_1
	v_mov_b32_e32 v4, v40
	v_mov_b32_e32 v5, v36
	v_mul_f32_e32 v22, v22, v22
	v_mul_f32_e32 v23, v23, v23
	v_mov_b32_e32 v24, v43
	v_mov_b32_e32 v25, v39
	v_cvt_f32_f16_e32 v26, v20
	v_cvt_f32_f16_e32 v28, v21
	s_waitcnt vmcnt(60)
	v_cvt_f32_f16_sdwa v31, v18 dst_sel:DWORD dst_unused:UNUSED_PAD src0_sel:WORD_1
	v_fma_f32 v4, v4, v4, v22
	v_fma_f32 v5, v5, v5, v23
	v_mov_b32_e32 v22, v42
	v_mov_b32_e32 v23, v38
	v_mul_f32_e32 v24, v24, v24
	v_mul_f32_e32 v25, v25, v25
	v_cvt_f32_f16_e32 v30, v18
	v_cvt_f32_f16_sdwa v33, v19 dst_sel:DWORD dst_unused:UNUSED_PAD src0_sel:WORD_1
	v_fma_f32 v22, v22, v22, v24
	v_fma_f32 v23, v23, v23, v25
	v_cvt_f32_f16_e32 v32, v19
	v_add_f32_e32 v4, v4, v22
	v_add_f32_e32 v5, v5, v23
	v_mov_b32_e32 v22, v27
	v_mov_b32_e32 v23, v29
	v_mov_b32_e32 v20, v26
	v_mov_b32_e32 v21, v28
	v_mul_f32_e32 v22, v22, v22
	v_mul_f32_e32 v23, v23, v23
	v_mul_f32_e32 v18, v31, v31
	v_fma_f32 v20, v20, v20, v22
	v_fma_f32 v21, v21, v21, v23
	v_fma_f32 v24, v30, v30, v18
	v_fma_f32 v25, v31, v31, v18
	v_mul_f32_e32 v18, v33, v33
	v_add_f32_e32 v22, v20, v21
	v_add_f32_e32 v23, v21, v20
	v_fma_f32 v34, v32, v32, v18
	v_fma_f32 v35, v33, v33, v18
	s_waitcnt vmcnt(59)
	v_cvt_f32_f16_sdwa v19, v16 dst_sel:DWORD dst_unused:UNUSED_PAD src0_sel:WORD_1
	v_cvt_f32_f16_e32 v18, v16
	v_cvt_f32_f16_sdwa v21, v17 dst_sel:DWORD dst_unused:UNUSED_PAD src0_sel:WORD_1
	v_cvt_f32_f16_e32 v20, v17
	v_pk_add_f32 v[4:5], v[4:5], v[4:5] op_sel:[0,1] op_sel_hi:[1,0]
	v_mul_f32_e32 v16, v18, v18
	v_mul_f32_e32 v17, v19, v19
	v_mul_f32_e32 v44, v20, v20
	v_mul_f32_e32 v45, v21, v21
	v_mov_b32_e32 v5, v16
	v_mov_b32_e32 v23, v17
	v_mov_b32_e32 v25, v44
	v_mov_b32_e32 v35, v45
	v_add_f32_e32 v4, v4, v22
	v_add_f32_e32 v5, v5, v23
	v_add_f32_e32 v16, v24, v34
	v_add_f32_e32 v17, v25, v35
	s_waitcnt vmcnt(58)
; __device__ __forceinline__ void norm_mod_phase2(const Args& a, Frame& F, const float* gain, const float* modl, int sh_off, int sc_off, int nrows, const float* slab_gate) {
;     ...
;     if (ML + nw < nrows) {
	v_cvt_f32_f16_sdwa v23, v14 dst_sel:DWORD dst_unused:UNUSED_PAD src0_sel:WORD_1
	v_cvt_f32_f16_sdwa v25, v15 dst_sel:DWORD dst_unused:UNUSED_PAD src0_sel:WORD_1
	v_cvt_f32_f16_e32 v22, v14
	v_cvt_f32_f16_e32 v24, v15
	v_add_f32_e32 v4, v4, v16
	v_add_f32_e32 v5, v5, v17
	v_mov_b32_e32 v14, v23
	v_mov_b32_e32 v15, v25
	v_add_f32_e32 v34, v4, v5
	v_add_f32_e32 v35, v5, v4
	v_mov_b32_e32 v4, v22
	v_mov_b32_e32 v5, v24
	v_mul_f32_e32 v14, v14, v14
	v_mul_f32_e32 v15, v15, v15
	s_waitcnt vmcnt(56)
	v_cvt_f32_f16_sdwa v17, v11 dst_sel:DWORD dst_unused:UNUSED_PAD src0_sel:WORD_1
	v_fma_f32 v4, v4, v4, v14
	v_fma_f32 v5, v5, v5, v15
	v_cvt_f32_f16_sdwa v15, v13 dst_sel:DWORD dst_unused:UNUSED_PAD src0_sel:WORD_1
	v_add_f32_e32 v44, v4, v5
	v_add_f32_e32 v45, v5, v4
	v_cvt_f32_f16_sdwa v5, v12 dst_sel:DWORD dst_unused:UNUSED_PAD src0_sel:WORD_1
	v_cvt_f32_f16_e32 v4, v12
	v_cvt_f32_f16_e32 v14, v13
	v_cvt_f32_f16_e32 v16, v11
	v_mul_f32_e32 v12, v5, v5
	v_fma_f32 v46, v4, v4, v12
	v_fma_f32 v47, v5, v5, v12
	v_mul_f32_e32 v12, v15, v15
	v_fma_f32 v48, v14, v14, v12
	v_fma_f32 v49, v15, v15, v12
	v_cvt_f32_f16_sdwa v13, v10 dst_sel:DWORD dst_unused:UNUSED_PAD src0_sel:WORD_1
	v_cvt_f32_f16_e32 v12, v10
	v_mul_f32_e32 v50, v16, v16
	v_mul_f32_e32 v51, v17, v17
	v_mul_f32_e32 v10, v12, v12
	v_mul_f32_e32 v11, v13, v13
	s_nop 0
	v_mov_b32_e32 v35, v10
	v_mov_b32_e32 v45, v11
	v_mov_b32_e32 v47, v50
	v_mov_b32_e32 v49, v51
	v_add_f32_e32 v10, v34, v44
	v_add_f32_e32 v11, v35, v45
	v_add_f32_e32 v34, v46, v48
	v_add_f32_e32 v35, v47, v49
	s_nop 0
	v_add_f32_e32 v10, v10, v34
	v_add_f32_e32 v11, v11, v35
	s_nop 0
	v_add_f32_e32 v10, v10, v11
	s_nop 1
	v_add_f32_dpp v10, v10, v10 quad_perm:[1,0,3,2] row_mask:0xf bank_mask:0xf bound_ctrl:1
	s_nop 1
	v_add_f32_dpp v10, v10, v10 quad_perm:[2,3,0,1] row_mask:0xf bank_mask:0xf bound_ctrl:1
	s_nop 1
	v_add_f32_dpp v10, v10, v10 row_half_mirror row_mask:0xf bank_mask:0xf bound_ctrl:1
	s_nop 1
	v_add_f32_dpp v10, v10, v10 row_mirror row_mask:0xf bank_mask:0xf bound_ctrl:1
	s_nop 0
	v_readlane_b32 s5, v10, 16
	v_readlane_b32 s11, v10, 48
	v_readlane_b32 s6, v10, 0
	v_readlane_b32 s7, v10, 32
	v_mov_b32_e32 v10, s5
	v_mov_b32_e32 v11, s11
	v_add_f32_e32 v10, s6, v10
	v_add_f32_e32 v11, s7, v11
	s_lshl_b32 s5, s10, 1
	v_add_f32_e32 v10, v10, v11
	v_fmamk_f32 v10, v10, 0x3a000000, v252
	v_cmp_gt_f32_e32 vcc, s55, v10
	v_mul_f32_e32 v11, 0x4f800000, v10
	s_and_b32 s5, s5, 0xffffe000
	v_cndmask_b32_e32 v10, v10, v11, vcc
	v_sqrt_f32_e32 v11, v10
	s_add_i32 s5, s5, 0
	s_cmpk_lt_i32 s4, 0x400
	v_add_u32_e32 v34, -1, v11
	v_fma_f32 v35, -v34, v11, v10
	v_cmp_ge_f32_e64 s[6:7], 0, v35
	v_add_u32_e32 v35, 1, v11
	s_nop 0
	v_cndmask_b32_e64 v34, v11, v34, s[6:7]
	v_fma_f32 v11, -v35, v11, v10
	v_cmp_lt_f32_e64 s[6:7], 0, v11
	s_nop 1
	v_cndmask_b32_e64 v11, v34, v35, s[6:7]
	v_mul_f32_e32 v34, 0x37800000, v11
	v_cndmask_b32_e32 v11, v11, v34, vcc
	v_cmp_class_f32_e32 vcc, v10, v253
	s_nop 1
	v_cndmask_b32_e32 v10, v11, v10, vcc
	v_div_scale_f32 v11, s[6:7], v10, v10, 1.0
	v_rcp_f32_e32 v34, v11
	s_nop 0
	v_fma_f32 v35, -v11, v34, 1.0
	v_fmac_f32_e32 v34, v35, v34
	v_div_scale_f32 v35, vcc, 1.0, v10, 1.0
	v_mul_f32_e32 v44, v35, v34
	v_fma_f32 v45, -v11, v44, v35
	v_fmac_f32_e32 v44, v45, v34
	v_fma_f32 v11, -v11, v44, v35
	v_div_fmas_f32 v11, v11, v34, v44
	v_div_fixup_f32 v34, v11, v10, 1.0
	v_mul_f32_e32 v48, v40, v34
	v_mul_f32_e32 v49, v41, v34
	v_mul_f32_e32 v50, v42, v34
	v_mul_f32_e32 v51, v43, v34
	v_add_u32_e32 v35, s5, v0
	ds_read_b128 v[40:43], v35
	ds_read_b128 v[44:47], v35 offset:40960
	v_lshl_add_u64 v[10:11], s[12:13], 1, v[2:3]
	v_lshl_add_u64 v[10:11], v[10:11], 0, v[6:7]
	v_mul_f32_e32 v4, v4, v34
	v_mul_f32_e32 v5, v5, v34
	v_mul_f32_e32 v14, v14, v34
	v_mul_f32_e32 v15, v15, v34
	s_waitcnt lgkmcnt(0)
	v_fma_f32 v42, v42, v50, v46
	v_fma_f32 v43, v43, v51, v47
	v_fma_f32 v40, v40, v48, v44
	v_fma_f32 v41, v41, v49, v45
	v_mul_f32_e32 v44, v36, v34
	v_mul_f32_e32 v45, v37, v34
	v_cvt_pk_bf16_f32 v40, v40, v41
	v_cvt_pk_bf16_f32 v41, v42, v43
	global_store_dwordx2 v[10:11], v[40:41], off
	v_mul_f32_e32 v46, v38, v34
	v_mul_f32_e32 v47, v39, v34
	ds_read_b128 v[36:39], v35 offset:1024
	ds_read_b128 v[40:43], v35 offset:41984
	s_waitcnt lgkmcnt(0)
	v_fma_f32 v38, v38, v46, v42
	v_fma_f32 v39, v39, v47, v43
	v_fma_f32 v36, v36, v44, v40
	v_fma_f32 v37, v37, v45, v41
	v_mul_f32_e32 v40, v26, v34
	v_mul_f32_e32 v41, v27, v34
	v_cvt_pk_bf16_f32 v36, v36, v37
	v_cvt_pk_bf16_f32 v37, v38, v39
	global_store_dwordx2 v[10:11], v[36:37], off offset:512
	v_mul_f32_e32 v42, v28, v34
	v_mul_f32_e32 v43, v29, v34
	ds_read_b128 v[26:29], v35 offset:2048
	ds_read_b128 v[36:39], v35 offset:43008
	s_waitcnt lgkmcnt(0)
	v_fma_f32 v28, v28, v42, v38
	v_fma_f32 v29, v29, v43, v39
	v_fma_f32 v26, v26, v40, v36
	v_fma_f32 v27, v27, v41, v37
	v_mul_f32_e32 v36, v30, v34
	v_mul_f32_e32 v37, v31, v34
	v_cvt_pk_bf16_f32 v26, v26, v27
	v_cvt_pk_bf16_f32 v27, v28, v29
	global_store_dwordx2 v[10:11], v[26:27], off offset:1024
	v_mul_f32_e32 v38, v32, v34
	v_mul_f32_e32 v39, v33, v34
	ds_read_b128 v[26:29], v35 offset:3072
	ds_read_b128 v[30:33], v35 offset:44032
	s_waitcnt lgkmcnt(0)
	v_fma_f32 v28, v38, v28, v32
	v_fma_f32 v29, v39, v29, v33
	v_fma_f32 v26, v36, v26, v30
	v_fma_f32 v27, v37, v27, v31
	v_mul_f32_e32 v30, v18, v34
	v_mul_f32_e32 v31, v19, v34
	v_cvt_pk_bf16_f32 v26, v26, v27
	v_cvt_pk_bf16_f32 v27, v28, v29
	global_store_dwordx2 v[10:11], v[26:27], off offset:1536
	v_mul_f32_e32 v32, v20, v34
	v_mul_f32_e32 v33, v21, v34
	ds_read_b128 v[18:21], v35 offset:4096
	ds_read_b128 v[26:29], v35 offset:45056
	s_waitcnt lgkmcnt(0)
; #define GAS __attribute__((address_space(1)))
; __device__ __forceinline__ unsigned xpk2(float lo, float hi) { if (XRES_F16) { const f32x2_t v = {lo, hi}; const f16x2_t h = __builtin_convertvector(v, f16x2_t); return __builtin_bit_cast(unsigned, h); } return pk2(lo, hi); }
; __device__ __forceinline__ float xlo(unsigned w) { if (XRES_F16) { const f16x2_t h = __builtin_bit_cast(f16x2_t, w); return (float)h[0]; } return __builtin_bit_cast(float, w << 16); }
; __device__ __forceinline__ float xhi(unsigned w) { if (XRES_F16) { const f16x2_t h = __builtin_bit_cast(f16x2_t, w); return (float)h[1]; } return __builtin_bit_cast(float, w & 0xffff0000u); }
; __device__ __forceinline__ void norm_mod_phase2(const Args& a, Frame& F, const float* gain, const float* modl, int sh_off, int sc_off, int nrows, const float* slab_gate) {
;     ...
;     if (ML + nw < nrows) {
;         const int r = ML + nw, rc = nw;
;         const GAS v2u* xr = (const GAS v2u*)(X + (size_t)r * D) + F.lane;
; #pragma unroll
;         for (int j = 0; j < 8; ++j) r0[j] = xr[64 * j];
;         if (slab_gate != nullptr) { const GAS f32x4* sl = (const GAS f32x4*)((const float*)(a.ws + WS_SLAB) + (size_t)rc * D) + F.lane;
; #pragma unroll
;             for (int j = 0; j < 8; ++j) { const f32x4 p = (sl[64 * j] + sl[64 * j + (size_t)MC * D / 4]) + (sl[64 * j + 2 * ((size_t)MC * D / 4)] + sl[64 * j + 3 * ((size_t)MC * D / 4)]);
;                 const f32x4 x = (f32x4){xlo(r0[j].x), xhi(r0[j].x), xlo(r0[j].y), xhi(r0[j].y)} + *(const GAS f32x4*)(slab_gate + 256 * j + 4 * F.lane) * p;
;                 v2u w; w.x = xpk2(x[0], x[1]); w.y = xpk2(x[2], x[3]); ((GAS v2u*)(X + (size_t)r * D) + F.lane)[64 * j] = w; r0[j] = w; } }
	v_fma_f32 v20, v32, v20, v28
	v_fma_f32 v21, v33, v21, v29
	v_fma_f32 v18, v30, v18, v26
	v_fma_f32 v19, v31, v19, v27
	v_mul_f32_e32 v26, v22, v34
	v_mul_f32_e32 v27, v23, v34
	v_cvt_pk_bf16_f32 v18, v18, v19
	v_cvt_pk_bf16_f32 v19, v20, v21
	global_store_dwordx2 v[10:11], v[18:19], off offset:2048
	v_mul_f32_e32 v28, v24, v34
	v_mul_f32_e32 v29, v25, v34
	ds_read_b128 v[18:21], v35 offset:5120
	ds_read_b128 v[22:25], v35 offset:46080
	s_waitcnt lgkmcnt(0)
	v_fma_f32 v20, v28, v20, v24
	v_fma_f32 v21, v29, v21, v25
	v_fma_f32 v18, v26, v18, v22
	v_fma_f32 v19, v27, v19, v23
	s_nop 0
	v_cvt_pk_bf16_f32 v18, v18, v19
	v_cvt_pk_bf16_f32 v19, v20, v21
	global_store_dwordx2 v[10:11], v[18:19], off offset:2560
	ds_read_b128 v[18:21], v35 offset:6144
	ds_read_b128 v[22:25], v35 offset:47104
	s_waitcnt lgkmcnt(0)
	v_fma_f32 v14, v14, v20, v24
	v_fma_f32 v15, v15, v21, v25
	v_fma_f32 v4, v4, v18, v22
	v_fma_f32 v5, v5, v19, v23
	v_mul_f32_e32 v20, v16, v34
	v_mul_f32_e32 v21, v17, v34
	v_cvt_pk_bf16_f32 v4, v4, v5
	v_cvt_pk_bf16_f32 v5, v14, v15
	global_store_dwordx2 v[10:11], v[4:5], off offset:3072
	v_mul_f32_e32 v4, v12, v34
	v_mul_f32_e32 v5, v13, v34
	ds_read_b128 v[12:15], v35 offset:7168
	ds_read_b128 v[16:19], v35 offset:48128
	s_waitcnt lgkmcnt(0)
	v_fma_f32 v14, v20, v14, v18
	v_fma_f32 v15, v21, v15, v19
	v_fma_f32 v4, v4, v12, v16
	v_fma_f32 v5, v5, v13, v17
	s_nop 0
	v_cvt_pk_bf16_f32 v4, v4, v5
	v_cvt_pk_bf16_f32 v5, v14, v15
	global_store_dwordx2 v[10:11], v[4:5], off offset:3584
	s_cbranch_scc0 .LBB0_223
	s_addk_i32 s4, 0x4000
	s_ashr_i32 s5, s4, 31
	s_lshl_b64 s[6:7], s[4:5], 12
	v_lshl_add_u64 v[4:5], v[8:9], 0, s[6:7]
	v_lshl_add_u64 v[18:19], v[4:5], 0, v[6:7]
	global_load_dwordx2 v[22:23], v[18:19], off
	global_load_dwordx2 v[20:21], v[18:19], off offset:512
	global_load_dwordx2 v[16:17], v[18:19], off offset:1024
	global_load_dwordx2 v[12:13], v[18:19], off offset:1536
	global_load_dwordx2 v[14:15], v[18:19], off offset:2048
	global_load_dwordx2 v[10:11], v[18:19], off offset:2560
	global_load_dwordx2 v[8:9], v[18:19], off offset:3072
	global_load_dwordx2 v[4:5], v[18:19], off offset:3584
	v_lshlrev_b32_e32 v40, 2, v143
	s_cmp_eq_u32 s76, 0
	s_cbranch_scc1 .LBB0_222
	v_mov_b32_e32 v24, s72
	v_mov_b32_e32 v25, s73
	v_lshl_add_u64 v[24:25], s[8:9], 2, v[24:25]
	v_lshl_add_u64 v[24:25], v[24:25], 0, v[0:1]
	v_lshlrev_b32_e32 v0, 2, v40
	v_lshl_add_u64 v[26:27], s[86:87], 0, v[0:1]
	v_add_co_u32_e32 v28, vcc, 0x58400000, v24
	s_nop 1
	v_addc_co_u32_e32 v29, vcc, 0, v25, vcc
	v_add_co_u32_e32 v30, vcc, 0x58c00000, v24
	s_nop 1
	v_addc_co_u32_e32 v31, vcc, 0, v25, vcc
	v_add_co_u32_e32 v32, vcc, 0x59400000, v24
	s_nop 1
	v_addc_co_u32_e32 v33, vcc, 0, v25, vcc
	v_add_co_u32_e32 v34, vcc, 0x59c00000, v24
	s_nop 1
	v_addc_co_u32_e32 v35, vcc, 0, v25, vcc
	v_add_co_u32_e32 v36, vcc, 0x58401000, v24
	s_nop 1
	v_addc_co_u32_e32 v37, vcc, 0, v25, vcc
	v_add_co_u32_e32 v38, vcc, 0x58c01000, v24
	s_nop 1
	v_addc_co_u32_e32 v39, vcc, 0, v25, vcc
	v_add_co_u32_e32 v42, vcc, 0x59401000, v24
	s_nop 1
	v_addc_co_u32_e32 v43, vcc, 0, v25, vcc
	v_add_co_u32_e32 v44, vcc, 0x59c01000, v24
	s_nop 1
	v_addc_co_u32_e32 v45, vcc, 0, v25, vcc
	v_add_co_u32_e32 v48, vcc, 0xffffe000, v26
	s_nop 1
	v_addc_co_u32_e32 v49, vcc, -1, v27, vcc
	v_add_co_u32_e32 v50, vcc, 0xfffff000, v26
	s_nop 1
	v_addc_co_u32_e32 v51, vcc, -1, v27, vcc
	global_load_dwordx4 v[94:97], v[28:29], off
	global_load_dwordx4 v[98:101], v[30:31], off
	global_load_dwordx4 v[102:105], v[32:33], off
	global_load_dwordx4 v[106:109], v[34:35], off
	global_load_dwordx4 v[110:113], v[48:49], off
	global_load_dwordx4 v[114:117], v[28:29], off offset:1024
	global_load_dwordx4 v[118:121], v[30:31], off offset:1024
	global_load_dwordx4 v[122:125], v[32:33], off offset:1024
	global_load_dwordx4 v[126:129], v[34:35], off offset:1024
	global_load_dwordx4 v[130:133], v[48:49], off offset:1024
	global_load_dwordx4 v[134:137], v[28:29], off offset:2048
	global_load_dwordx4 v[138:141], v[30:31], off offset:2048
	global_load_dwordx4 v[142:145], v[32:33], off offset:2048
	global_load_dwordx4 v[146:149], v[34:35], off offset:2048
	global_load_dwordx4 v[150:153], v[48:49], off offset:2048
	global_load_dwordx4 v[154:157], v[28:29], off offset:3072
	global_load_dwordx4 v[158:161], v[30:31], off offset:3072
	global_load_dwordx4 v[162:165], v[32:33], off offset:3072
	global_load_dwordx4 v[170:173], v[34:35], off offset:3072
	global_load_dwordx4 v[174:177], v[48:49], off offset:3072
	s_waitcnt vmcnt(15)
	v_add_f32_e32 v220, v94, v98
	v_add_f32_e32 v221, v95, v99
	v_add_f32_e32 v222, v96, v100
	v_add_f32_e32 v223, v97, v101
	v_add_f32_e32 v224, v102, v106
	v_add_f32_e32 v225, v103, v107
	v_add_f32_e32 v226, v104, v108
	v_add_f32_e32 v227, v105, v109
	v_cvt_f32_f16_e32 v232, v22
	v_cvt_f32_f16_sdwa v233, v22 dst_sel:DWORD dst_unused:UNUSED_PAD src0_sel:WORD_1
	v_cvt_f32_f16_e32 v234, v23
	v_cvt_f32_f16_sdwa v235, v23 dst_sel:DWORD dst_unused:UNUSED_PAD src0_sel:WORD_1
	v_add_f32_e32 v228, v220, v224
	v_add_f32_e32 v229, v221, v225
	v_add_f32_e32 v230, v222, v226
	v_add_f32_e32 v231, v223, v227
	s_nop 1
	v_fma_f32 v236, v110, v228, v232
	v_fma_f32 v237, v111, v229, v233
	v_fma_f32 v238, v112, v230, v234
	v_fma_f32 v239, v113, v231, v235
	s_nop 1
	v_cvt_pk_f16_f32 v22, v236, v237
	v_cvt_pk_f16_f32 v23, v238, v239
	global_store_dwordx2 v[18:19], v[22:23], off
	global_load_dwordx4 v[94:97], v[36:37], off
	global_load_dwordx4 v[98:101], v[38:39], off
	global_load_dwordx4 v[102:105], v[42:43], off
	global_load_dwordx4 v[106:109], v[44:45], off
	global_load_dwordx4 v[110:113], v[50:51], off
	s_waitcnt vmcnt(16)
; #define GAS __attribute__((address_space(1)))
; __device__ __forceinline__ unsigned xpk2(float lo, float hi) { if (XRES_F16) { const f32x2_t v = {lo, hi}; const f16x2_t h = __builtin_convertvector(v, f16x2_t); return __builtin_bit_cast(unsigned, h); } return pk2(lo, hi); }
; __device__ __forceinline__ float xlo(unsigned w) { if (XRES_F16) { const f16x2_t h = __builtin_bit_cast(f16x2_t, w); return (float)h[0]; } return __builtin_bit_cast(float, w << 16); }
; __device__ __forceinline__ float xhi(unsigned w) { if (XRES_F16) { const f16x2_t h = __builtin_bit_cast(f16x2_t, w); return (float)h[1]; } return __builtin_bit_cast(float, w & 0xffff0000u); }
; __device__ __forceinline__ void norm_mod_phase2(const Args& a, Frame& F, const float* gain, const float* modl, int sh_off, int sc_off, int nrows, const float* slab_gate) {
;     ...
;         if (slab_gate != nullptr) { const GAS f32x4* sl = (const GAS f32x4*)((const float*)(a.ws + WS_SLAB) + (size_t)rc * D) + F.lane;
; #pragma unroll
;             for (int j = 0; j < 8; ++j) { const f32x4 p = (sl[64 * j] + sl[64 * j + (size_t)MC * D / 4]) + (sl[64 * j + 2 * ((size_t)MC * D / 4)] + sl[64 * j + 3 * ((size_t)MC * D / 4)]);
;                 const f32x4 x = (f32x4){xlo(r0[j].x), xhi(r0[j].x), xlo(r0[j].y), xhi(r0[j].y)} + *(const GAS f32x4*)(slab_gate + 256 * j + 4 * F.lane) * p;
;                 v2u w; w.x = xpk2(x[0], x[1]); w.y = xpk2(x[2], x[3]); ((GAS v2u*)(X + (size_t)r * D) + F.lane)[64 * j] = w; r0[j] = w; } }
	v_add_f32_e32 v220, v114, v118
	v_add_f32_e32 v221, v115, v119
	v_add_f32_e32 v222, v116, v120
	v_add_f32_e32 v223, v117, v121
	v_add_f32_e32 v224, v122, v126
	v_add_f32_e32 v225, v123, v127
	v_add_f32_e32 v226, v124, v128
	v_add_f32_e32 v227, v125, v129
	v_cvt_f32_f16_e32 v232, v20
	v_cvt_f32_f16_sdwa v233, v20 dst_sel:DWORD dst_unused:UNUSED_PAD src0_sel:WORD_1
	v_cvt_f32_f16_e32 v234, v21
	v_cvt_f32_f16_sdwa v235, v21 dst_sel:DWORD dst_unused:UNUSED_PAD src0_sel:WORD_1
	v_add_f32_e32 v228, v220, v224
	v_add_f32_e32 v229, v221, v225
	v_add_f32_e32 v230, v222, v226
	v_add_f32_e32 v231, v223, v227
	s_nop 1
	v_fma_f32 v236, v130, v228, v232
	v_fma_f32 v237, v131, v229, v233
	v_fma_f32 v238, v132, v230, v234
	v_fma_f32 v239, v133, v231, v235
	s_nop 1
	v_cvt_pk_f16_f32 v20, v236, v237
	v_cvt_pk_f16_f32 v21, v238, v239
	global_store_dwordx2 v[18:19], v[20:21], off offset:512
	global_load_dwordx4 v[114:117], v[36:37], off offset:1024
	global_load_dwordx4 v[118:121], v[38:39], off offset:1024
	global_load_dwordx4 v[122:125], v[42:43], off offset:1024
	global_load_dwordx4 v[126:129], v[44:45], off offset:1024
	global_load_dwordx4 v[130:133], v[50:51], off offset:1024
	s_waitcnt vmcnt(17)
	v_add_f32_e32 v220, v134, v138
	v_add_f32_e32 v221, v135, v139
	v_add_f32_e32 v222, v136, v140
	v_add_f32_e32 v223, v137, v141
	v_add_f32_e32 v224, v142, v146
	v_add_f32_e32 v225, v143, v147
	v_add_f32_e32 v226, v144, v148
	v_add_f32_e32 v227, v145, v149
	v_cvt_f32_f16_e32 v232, v16
	v_cvt_f32_f16_sdwa v233, v16 dst_sel:DWORD dst_unused:UNUSED_PAD src0_sel:WORD_1
	v_cvt_f32_f16_e32 v234, v17
	v_cvt_f32_f16_sdwa v235, v17 dst_sel:DWORD dst_unused:UNUSED_PAD src0_sel:WORD_1
	v_add_f32_e32 v228, v220, v224
	v_add_f32_e32 v229, v221, v225
	v_add_f32_e32 v230, v222, v226
	v_add_f32_e32 v231, v223, v227
	s_nop 1
	v_fma_f32 v236, v150, v228, v232
	v_fma_f32 v237, v151, v229, v233
	v_fma_f32 v238, v152, v230, v234
	v_fma_f32 v239, v153, v231, v235
	s_nop 1
	v_cvt_pk_f16_f32 v16, v236, v237
	v_cvt_pk_f16_f32 v17, v238, v239
	global_store_dwordx2 v[18:19], v[16:17], off offset:1024
	global_load_dwordx4 v[134:137], v[36:37], off offset:2048
	global_load_dwordx4 v[138:141], v[38:39], off offset:2048
	global_load_dwordx4 v[142:145], v[42:43], off offset:2048
	global_load_dwordx4 v[146:149], v[44:45], off offset:2048
	global_load_dwordx4 v[150:153], v[50:51], off offset:2048
	s_waitcnt vmcnt(18)
	v_add_f32_e32 v220, v154, v158
	v_add_f32_e32 v221, v155, v159
	v_add_f32_e32 v222, v156, v160
	v_add_f32_e32 v223, v157, v161
	v_add_f32_e32 v224, v162, v170
	v_add_f32_e32 v225, v163, v171
	v_add_f32_e32 v226, v164, v172
	v_add_f32_e32 v227, v165, v173
	v_cvt_f32_f16_e32 v232, v12
	v_cvt_f32_f16_sdwa v233, v12 dst_sel:DWORD dst_unused:UNUSED_PAD src0_sel:WORD_1
	v_cvt_f32_f16_e32 v234, v13
	v_cvt_f32_f16_sdwa v235, v13 dst_sel:DWORD dst_unused:UNUSED_PAD src0_sel:WORD_1
	v_add_f32_e32 v228, v220, v224
	v_add_f32_e32 v229, v221, v225
	v_add_f32_e32 v230, v222, v226
	v_add_f32_e32 v231, v223, v227
	s_nop 1
	v_fma_f32 v236, v174, v228, v232
	v_fma_f32 v237, v175, v229, v233
	v_fma_f32 v238, v176, v230, v234
	v_fma_f32 v239, v177, v231, v235
	s_nop 1
	v_cvt_pk_f16_f32 v12, v236, v237
	v_cvt_pk_f16_f32 v13, v238, v239
	global_store_dwordx2 v[18:19], v[12:13], off offset:1536
	global_load_dwordx4 v[154:157], v[36:37], off offset:3072
	global_load_dwordx4 v[158:161], v[38:39], off offset:3072
	global_load_dwordx4 v[162:165], v[42:43], off offset:3072
	global_load_dwordx4 v[170:173], v[44:45], off offset:3072
	global_load_dwordx4 v[174:177], v[50:51], off offset:3072
	s_waitcnt vmcnt(18)
	v_add_f32_e32 v220, v94, v98
	v_add_f32_e32 v221, v95, v99
	v_add_f32_e32 v222, v96, v100
	v_add_f32_e32 v223, v97, v101
	v_add_f32_e32 v224, v102, v106
	v_add_f32_e32 v225, v103, v107
	v_add_f32_e32 v226, v104, v108
	v_add_f32_e32 v227, v105, v109
	v_cvt_f32_f16_e32 v232, v14
	v_cvt_f32_f16_sdwa v233, v14 dst_sel:DWORD dst_unused:UNUSED_PAD src0_sel:WORD_1
	v_cvt_f32_f16_e32 v234, v15
	v_cvt_f32_f16_sdwa v235, v15 dst_sel:DWORD dst_unused:UNUSED_PAD src0_sel:WORD_1
	v_add_f32_e32 v228, v220, v224
	v_add_f32_e32 v229, v221, v225
	v_add_f32_e32 v230, v222, v226
	v_add_f32_e32 v231, v223, v227
	s_nop 1
	v_fma_f32 v236, v110, v228, v232
	v_fma_f32 v237, v111, v229, v233
	v_fma_f32 v238, v112, v230, v234
	v_fma_f32 v239, v113, v231, v235
	s_nop 1
	v_cvt_pk_f16_f32 v14, v236, v237
	v_cvt_pk_f16_f32 v15, v238, v239
	global_store_dwordx2 v[18:19], v[14:15], off offset:2048
	s_waitcnt vmcnt(13)
	v_add_f32_e32 v220, v114, v118
	v_add_f32_e32 v221, v115, v119
	v_add_f32_e32 v222, v116, v120
	v_add_f32_e32 v223, v117, v121
	v_add_f32_e32 v224, v122, v126
	v_add_f32_e32 v225, v123, v127
	v_add_f32_e32 v226, v124, v128
	v_add_f32_e32 v227, v125, v129
	v_cvt_f32_f16_e32 v232, v10
	v_cvt_f32_f16_sdwa v233, v10 dst_sel:DWORD dst_unused:UNUSED_PAD src0_sel:WORD_1
	v_cvt_f32_f16_e32 v234, v11
	v_cvt_f32_f16_sdwa v235, v11 dst_sel:DWORD dst_unused:UNUSED_PAD src0_sel:WORD_1
	v_add_f32_e32 v228, v220, v224
	v_add_f32_e32 v229, v221, v225
	v_add_f32_e32 v230, v222, v226
	v_add_f32_e32 v231, v223, v227
	s_nop 1
	v_fma_f32 v236, v130, v228, v232
	v_fma_f32 v237, v131, v229, v233
	v_fma_f32 v238, v132, v230, v234
	v_fma_f32 v239, v133, v231, v235
	s_nop 1
	v_cvt_pk_f16_f32 v10, v236, v237
	v_cvt_pk_f16_f32 v11, v238, v239
	global_store_dwordx2 v[18:19], v[10:11], off offset:2560
	s_waitcnt vmcnt(8)
; #define GAS __attribute__((address_space(1)))
; __device__ __forceinline__ unsigned xpk2(float lo, float hi) { if (XRES_F16) { const f32x2_t v = {lo, hi}; const f16x2_t h = __builtin_convertvector(v, f16x2_t); return __builtin_bit_cast(unsigned, h); } return pk2(lo, hi); }
; __device__ __forceinline__ float xlo(unsigned w) { if (XRES_F16) { const f16x2_t h = __builtin_bit_cast(f16x2_t, w); return (float)h[0]; } return __builtin_bit_cast(float, w << 16); }
; __device__ __forceinline__ float xhi(unsigned w) { if (XRES_F16) { const f16x2_t h = __builtin_bit_cast(f16x2_t, w); return (float)h[1]; } return __builtin_bit_cast(float, w & 0xffff0000u); }
; __device__ __forceinline__ void norm_mod_phase2(const Args& a, Frame& F, const float* gain, const float* modl, int sh_off, int sc_off, int nrows, const float* slab_gate) {
;     ...
;             for (int j = 0; j < 8; ++j) { const f32x4 p = (sl[64 * j] + sl[64 * j + (size_t)MC * D / 4]) + (sl[64 * j + 2 * ((size_t)MC * D / 4)] + sl[64 * j + 3 * ((size_t)MC * D / 4)]);
;                 const f32x4 x = (f32x4){xlo(r0[j].x), xhi(r0[j].x), xlo(r0[j].y), xhi(r0[j].y)} + *(const GAS f32x4*)(slab_gate + 256 * j + 4 * F.lane) * p;
;                 v2u w; w.x = xpk2(x[0], x[1]); w.y = xpk2(x[2], x[3]); ((GAS v2u*)(X + (size_t)r * D) + F.lane)[64 * j] = w; r0[j] = w; } }
	v_add_f32_e32 v220, v134, v138
	v_add_f32_e32 v221, v135, v139
	v_add_f32_e32 v222, v136, v140
	v_add_f32_e32 v223, v137, v141
	v_add_f32_e32 v224, v142, v146
	v_add_f32_e32 v225, v143, v147
	v_add_f32_e32 v226, v144, v148
	v_add_f32_e32 v227, v145, v149
	v_cvt_f32_f16_e32 v232, v8
	v_cvt_f32_f16_sdwa v233, v8 dst_sel:DWORD dst_unused:UNUSED_PAD src0_sel:WORD_1
	v_cvt_f32_f16_e32 v234, v9
	v_cvt_f32_f16_sdwa v235, v9 dst_sel:DWORD dst_unused:UNUSED_PAD src0_sel:WORD_1
	v_add_f32_e32 v228, v220, v224
	v_add_f32_e32 v229, v221, v225
	v_add_f32_e32 v230, v222, v226
	v_add_f32_e32 v231, v223, v227
	s_nop 1
	v_fma_f32 v236, v150, v228, v232
	v_fma_f32 v237, v151, v229, v233
	v_fma_f32 v238, v152, v230, v234
	v_fma_f32 v239, v153, v231, v235
	s_nop 1
	v_cvt_pk_f16_f32 v8, v236, v237
	v_cvt_pk_f16_f32 v9, v238, v239
	global_store_dwordx2 v[18:19], v[8:9], off offset:3072
	s_waitcnt vmcnt(3)
	v_add_f32_e32 v220, v154, v158
	v_add_f32_e32 v221, v155, v159
	v_add_f32_e32 v222, v156, v160
	v_add_f32_e32 v223, v157, v161
	v_add_f32_e32 v224, v162, v170
	v_add_f32_e32 v225, v163, v171
	v_add_f32_e32 v226, v164, v172
	v_add_f32_e32 v227, v165, v173
	v_cvt_f32_f16_e32 v232, v4
	v_cvt_f32_f16_sdwa v233, v4 dst_sel:DWORD dst_unused:UNUSED_PAD src0_sel:WORD_1
	v_cvt_f32_f16_e32 v234, v5
	v_cvt_f32_f16_sdwa v235, v5 dst_sel:DWORD dst_unused:UNUSED_PAD src0_sel:WORD_1
	v_add_f32_e32 v228, v220, v224
	v_add_f32_e32 v229, v221, v225
	v_add_f32_e32 v230, v222, v226
	v_add_f32_e32 v231, v223, v227
	s_nop 1
	v_fma_f32 v236, v174, v228, v232
	v_fma_f32 v237, v175, v229, v233
	v_fma_f32 v238, v176, v230, v234
	v_fma_f32 v239, v177, v231, v235
	s_nop 1
	v_cvt_pk_f16_f32 v4, v236, v237
	v_cvt_pk_f16_f32 v5, v238, v239
	global_store_dwordx2 v[18:19], v[4:5], off offset:3584
.LBB0_222:
	s_waitcnt vmcnt(7)
	v_cvt_f32_f16_sdwa v37, v22 dst_sel:DWORD dst_unused:UNUSED_PAD src0_sel:WORD_1
	s_waitcnt vmcnt(6)
	v_cvt_f32_f16_sdwa v33, v20 dst_sel:DWORD dst_unused:UNUSED_PAD src0_sel:WORD_1
	v_cvt_f32_f16_e32 v36, v22
	v_cvt_f32_f16_sdwa v39, v23 dst_sel:DWORD dst_unused:UNUSED_PAD src0_sel:WORD_1
	v_cvt_f32_f16_e32 v32, v20
	v_cvt_f32_f16_sdwa v35, v21 dst_sel:DWORD dst_unused:UNUSED_PAD src0_sel:WORD_1
	v_cvt_f32_f16_e32 v38, v23
	v_cvt_f32_f16_e32 v34, v21
	v_mov_b32_e32 v20, v37
	v_mov_b32_e32 v21, v33
	v_mov_b32_e32 v18, v36
	v_mov_b32_e32 v19, v32
	v_mul_f32_e32 v20, v20, v20
	v_mul_f32_e32 v21, v21, v21
	v_mov_b32_e32 v22, v39
	v_mov_b32_e32 v23, v35
	s_waitcnt vmcnt(5)
	v_cvt_f32_f16_sdwa v25, v16 dst_sel:DWORD dst_unused:UNUSED_PAD src0_sel:WORD_1
	v_cvt_f32_f16_sdwa v27, v17 dst_sel:DWORD dst_unused:UNUSED_PAD src0_sel:WORD_1
	v_fma_f32 v18, v18, v18, v20
	v_fma_f32 v19, v19, v19, v21
	v_mov_b32_e32 v20, v38
	v_mov_b32_e32 v21, v34
	v_mul_f32_e32 v22, v22, v22
	v_mul_f32_e32 v23, v23, v23
	v_cvt_f32_f16_e32 v24, v16
	v_cvt_f32_f16_e32 v26, v17
	v_fma_f32 v20, v20, v20, v22
	v_fma_f32 v21, v21, v21, v23
	s_waitcnt vmcnt(4)
	v_cvt_f32_f16_e32 v28, v12
	v_add_f32_e32 v18, v18, v20
	v_add_f32_e32 v19, v19, v21
	v_mov_b32_e32 v16, v24
	v_add_f32_e32 v20, v18, v18
	v_add_f32_e32 v21, v18, v19
	v_mov_b32_e32 v18, v25
	v_mov_b32_e32 v19, v27
	v_mov_b32_e32 v17, v26
	v_mul_f32_e32 v18, v18, v18
	v_mul_f32_e32 v19, v19, v19
	v_cvt_f32_f16_sdwa v29, v12 dst_sel:DWORD dst_unused:UNUSED_PAD src0_sel:WORD_1
	v_fma_f32 v16, v16, v16, v18
	v_fma_f32 v17, v17, v17, v19
	v_cvt_f32_f16_e32 v30, v13
	s_waitcnt vmcnt(3)
	v_cvt_f32_f16_sdwa v19, v15 dst_sel:DWORD dst_unused:UNUSED_PAD src0_sel:WORD_1
	v_cvt_f32_f16_e32 v18, v15
	v_add_f32_e32 v22, v16, v16
	v_add_f32_e32 v23, v16, v17
	v_cvt_f32_f16_sdwa v31, v13 dst_sel:DWORD dst_unused:UNUSED_PAD src0_sel:WORD_1
	v_cvt_f32_f16_sdwa v17, v14 dst_sel:DWORD dst_unused:UNUSED_PAD src0_sel:WORD_1
	v_cvt_f32_f16_e32 v16, v14
	v_mul_f32_e32 v0, v28, v28
	v_fma_f32 v12, v28, v28, v0
	v_fma_f32 v13, v29, v29, v0
	v_mul_f32_e32 v0, v30, v30
	v_mul_f32_e32 v44, v18, v18
	v_mul_f32_e32 v45, v19, v19
	v_fma_f32 v42, v30, v30, v0
	v_fma_f32 v43, v31, v31, v0
	v_mul_f32_e32 v14, v16, v16
	v_mul_f32_e32 v15, v17, v17
	v_mov_b32_e32 v22, v44
	v_mov_b32_e32 v20, v45
	v_mov_b32_e32 v12, v14
	v_mov_b32_e32 v42, v15
	v_add_f32_e32 v14, v22, v20
	v_add_f32_e32 v15, v23, v21
	s_waitcnt vmcnt(2)
	v_cvt_f32_f16_sdwa v21, v10 dst_sel:DWORD dst_unused:UNUSED_PAD src0_sel:WORD_1
	v_cvt_f32_f16_sdwa v23, v11 dst_sel:DWORD dst_unused:UNUSED_PAD src0_sel:WORD_1
	v_cvt_f32_f16_e32 v20, v10
	v_cvt_f32_f16_e32 v22, v11
	v_add_f32_e32 v12, v12, v42
	v_add_f32_e32 v13, v13, v43
	s_lshl_b64 s[4:5], s[4:5], 11
	v_add_f32_e32 v12, v12, v14
	v_add_f32_e32 v13, v13, v15
	v_mov_b32_e32 v10, v20
	v_add_f32_e32 v42, v12, v12
	v_add_f32_e32 v43, v12, v13
	v_mov_b32_e32 v12, v21
	v_mov_b32_e32 v13, v23
	v_mov_b32_e32 v11, v22
	v_mul_f32_e32 v12, v12, v12
	v_mul_f32_e32 v13, v13, v13
	s_waitcnt vmcnt(0)
; template <int CTRL> __device__ __forceinline__ float dpp_mov(float v) { return __builtin_bit_cast(float, __builtin_amdgcn_update_dpp(0, __builtin_bit_cast(int, v), CTRL, 0xF, 0xF, true)); }
; __device__ __forceinline__ float wave_sum(float v) {
;     v += dpp_mov<0xB1>(v);
;     v += dpp_mov<0x4E>(v);
;     v += dpp_mov<0x141>(v);
;     v += dpp_mov<0x140>(v);
;     const int iv = __builtin_bit_cast(int, v);
;     const float a = __builtin_bit_cast(float, __builtin_amdgcn_readlane(iv, 0)), b = __builtin_bit_cast(float, __builtin_amdgcn_readlane(iv, 16));
;     const float c = __builtin_bit_cast(float, __builtin_amdgcn_readlane(iv, 32)), d = __builtin_bit_cast(float, __builtin_amdgcn_readlane(iv, 48));
;     return (a + b) + (c + d);
; }
	v_cvt_f32_f16_sdwa v15, v5 dst_sel:DWORD dst_unused:UNUSED_PAD src0_sel:WORD_1
	v_fma_f32 v10, v10, v10, v12
	v_fma_f32 v11, v11, v11, v13
	v_cvt_f32_f16_e32 v12, v9
	v_add_f32_e32 v44, v10, v10
	v_add_f32_e32 v45, v10, v11
	v_cvt_f32_f16_e32 v10, v8
	v_cvt_f32_f16_sdwa v11, v8 dst_sel:DWORD dst_unused:UNUSED_PAD src0_sel:WORD_1
	v_cvt_f32_f16_sdwa v13, v9 dst_sel:DWORD dst_unused:UNUSED_PAD src0_sel:WORD_1
	v_cvt_f32_f16_sdwa v9, v4 dst_sel:DWORD dst_unused:UNUSED_PAD src0_sel:WORD_1
	v_cvt_f32_f16_e32 v8, v4
	v_cvt_f32_f16_e32 v14, v5
	v_mul_f32_e32 v0, v10, v10
	v_fma_f32 v46, v10, v10, v0
	v_fma_f32 v47, v11, v11, v0
	v_mul_f32_e32 v0, v12, v12
	v_fma_f32 v48, v12, v12, v0
	v_fma_f32 v49, v13, v13, v0
	v_mul_f32_e32 v4, v8, v8
	v_mul_f32_e32 v5, v9, v9
	v_mul_f32_e32 v50, v14, v14
	v_mul_f32_e32 v51, v15, v15
	v_mov_b32_e32 v46, v4
	v_mov_b32_e32 v48, v5
	v_mov_b32_e32 v44, v50
	v_mov_b32_e32 v42, v51
	v_add_f32_e32 v4, v46, v48
	v_add_f32_e32 v5, v47, v49
	v_add_f32_e32 v42, v44, v42
	v_add_f32_e32 v43, v45, v43
	v_lshl_add_u32 v40, v40, 2, 0
	v_add_f32_e32 v4, v4, v42
	v_add_f32_e32 v5, v5, v43
	v_lshl_add_u64 v[2:3], s[4:5], 1, v[2:3]
	v_add_f32_e32 v0, v4, v5
	s_nop 1
	v_add_f32_dpp v0, v0, v0 quad_perm:[1,0,3,2] row_mask:0xf bank_mask:0xf bound_ctrl:1
	s_nop 1
	v_add_f32_dpp v0, v0, v0 quad_perm:[2,3,0,1] row_mask:0xf bank_mask:0xf bound_ctrl:1
	s_nop 1
	v_add_f32_dpp v0, v0, v0 row_half_mirror row_mask:0xf bank_mask:0xf bound_ctrl:1
	s_nop 1
	v_add_f32_dpp v0, v0, v0 row_mirror row_mask:0xf bank_mask:0xf bound_ctrl:1
	s_nop 0
	v_readlane_b32 s8, v0, 16
	v_readlane_b32 s9, v0, 48
	v_readlane_b32 s6, v0, 0
	v_readlane_b32 s7, v0, 32
	v_mov_b32_e32 v4, s8
	v_mov_b32_e32 v5, s9
	v_add_f32_e32 v4, s6, v4
	v_add_f32_e32 v5, s7, v5
	s_nop 0
	v_add_f32_e32 v0, v4, v5
	v_fmamk_f32 v0, v0, 0x3a000000, v252
	v_cmp_gt_f32_e32 vcc, s55, v0
	v_mul_f32_e32 v4, 0x4f800000, v0
	s_nop 0
	v_cndmask_b32_e32 v0, v0, v4, vcc
	v_sqrt_f32_e32 v4, v0
	s_nop 0
	v_add_u32_e32 v5, -1, v4
	v_fma_f32 v7, -v5, v4, v0
	v_cmp_ge_f32_e64 s[6:7], 0, v7
	v_add_u32_e32 v7, 1, v4
	s_nop 0
	v_cndmask_b32_e64 v5, v4, v5, s[6:7]
	v_fma_f32 v4, -v7, v4, v0
	v_cmp_lt_f32_e64 s[6:7], 0, v4
	s_nop 1
	v_cndmask_b32_e64 v4, v5, v7, s[6:7]
	v_mul_f32_e32 v5, 0x37800000, v4
	v_cndmask_b32_e32 v4, v4, v5, vcc
	v_cmp_class_f32_e32 vcc, v0, v253
	s_nop 1
	v_cndmask_b32_e32 v0, v4, v0, vcc
	v_div_scale_f32 v4, s[6:7], v0, v0, 1.0
	v_rcp_f32_e32 v5, v4
	s_nop 0
	v_fma_f32 v7, -v4, v5, 1.0
	v_fmac_f32_e32 v5, v7, v5
	v_div_scale_f32 v7, vcc, 1.0, v0, 1.0
	v_mul_f32_e32 v41, v7, v5
	v_fma_f32 v42, -v4, v41, v7
	v_fmac_f32_e32 v41, v42, v5
	v_fma_f32 v4, -v4, v41, v7
	v_div_fmas_f32 v4, v4, v5, v41
	v_div_fixup_f32 v0, v4, v0, 1.0
	v_mov_b32_e32 v7, v1
	v_add_u32_e32 v41, 0x12000, v40
	v_lshl_add_u64 v[2:3], v[2:3], 0, v[6:7]
	v_mul_f32_e32 v42, v36, v0
	v_mul_f32_e32 v43, v37, v0
	v_mul_f32_e32 v44, v38, v0
	v_mul_f32_e32 v45, v39, v0
	ds_read_b128 v[4:7], v40 offset:32768
	ds_read_b128 v[36:39], v41
	v_mul_f32_e32 v28, v28, v0
	v_mul_f32_e32 v29, v29, v0
	v_mul_f32_e32 v30, v30, v0
	v_mul_f32_e32 v31, v31, v0
	v_mul_f32_e32 v20, v20, v0
	v_mul_f32_e32 v21, v21, v0
	v_mul_f32_e32 v22, v22, v0
	v_mul_f32_e32 v23, v23, v0
	s_waitcnt lgkmcnt(0)
	v_fma_f32 v6, v6, v44, v38
	v_fma_f32 v7, v7, v45, v39
	v_fma_f32 v4, v4, v42, v36
	v_fma_f32 v5, v5, v43, v37
	v_mul_f32_e32 v36, v32, v0
	v_mul_f32_e32 v37, v33, v0
	v_cvt_pk_bf16_f32 v4, v4, v5
	v_cvt_pk_bf16_f32 v5, v6, v7
	global_store_dwordx2 v[2:3], v[4:5], off
	v_mul_f32_e32 v38, v34, v0
	v_mul_f32_e32 v39, v35, v0
	ds_read_b128 v[4:7], v40 offset:33792
	ds_read_b128 v[32:35], v41 offset:1024
	v_mul_f32_e32 v14, v14, v0
	v_mul_f32_e32 v15, v15, v0
	s_waitcnt lgkmcnt(0)
	v_fma_f32 v6, v6, v38, v34
	v_fma_f32 v7, v7, v39, v35
	v_fma_f32 v4, v4, v36, v32
	v_fma_f32 v5, v5, v37, v33
	v_mul_f32_e32 v32, v24, v0
	v_mul_f32_e32 v33, v25, v0
	v_cvt_pk_bf16_f32 v4, v4, v5
	v_cvt_pk_bf16_f32 v5, v6, v7
	global_store_dwordx2 v[2:3], v[4:5], off offset:512
	v_mul_f32_e32 v34, v26, v0
	v_mul_f32_e32 v35, v27, v0
	ds_read_b128 v[4:7], v40 offset:34816
	ds_read_b128 v[24:27], v41 offset:2048
	s_waitcnt lgkmcnt(0)
	v_fma_f32 v6, v6, v34, v26
	v_fma_f32 v7, v7, v35, v27
	v_fma_f32 v4, v4, v32, v24
	v_fma_f32 v5, v5, v33, v25
	s_nop 0
	v_cvt_pk_bf16_f32 v4, v4, v5
	v_cvt_pk_bf16_f32 v5, v6, v7
	global_store_dwordx2 v[2:3], v[4:5], off offset:1024
	ds_read_b128 v[4:7], v40 offset:35840
	ds_read_b128 v[24:27], v41 offset:3072
	s_waitcnt lgkmcnt(0)
	v_fma_f32 v6, v30, v6, v26
	v_fma_f32 v7, v31, v7, v27
	v_fma_f32 v4, v28, v4, v24
	v_fma_f32 v5, v29, v5, v25
	v_mul_f32_e32 v24, v16, v0
	v_mul_f32_e32 v25, v17, v0
	v_cvt_pk_bf16_f32 v4, v4, v5
	v_cvt_pk_bf16_f32 v5, v6, v7
	global_store_dwordx2 v[2:3], v[4:5], off offset:1536
	v_mul_f32_e32 v26, v18, v0
	v_mul_f32_e32 v27, v19, v0
	ds_read_b128 v[4:7], v40 offset:36864
	ds_read_b128 v[16:19], v41 offset:4096
	s_waitcnt lgkmcnt(0)
	v_fma_f32 v6, v26, v6, v18
	v_fma_f32 v7, v27, v7, v19
	v_fma_f32 v4, v24, v4, v16
	v_fma_f32 v5, v25, v5, v17
	s_nop 0
	v_cvt_pk_bf16_f32 v4, v4, v5
	v_cvt_pk_bf16_f32 v5, v6, v7
	global_store_dwordx2 v[2:3], v[4:5], off offset:2048
	ds_read_b128 v[4:7], v40 offset:37888
	ds_read_b128 v[16:19], v41 offset:5120
	s_waitcnt lgkmcnt(0)
	v_fma_f32 v6, v22, v6, v18
	v_fma_f32 v7, v23, v7, v19
	v_fma_f32 v4, v20, v4, v16
	v_fma_f32 v5, v21, v5, v17
	v_mul_f32_e32 v16, v10, v0
	v_mul_f32_e32 v17, v11, v0
	v_cvt_pk_bf16_f32 v4, v4, v5
	v_cvt_pk_bf16_f32 v5, v6, v7
	global_store_dwordx2 v[2:3], v[4:5], off offset:2560
	v_mul_f32_e32 v18, v12, v0
	v_mul_f32_e32 v19, v13, v0
	ds_read_b128 v[4:7], v40 offset:38912
	ds_read_b128 v[10:13], v41 offset:6144
	s_waitcnt lgkmcnt(0)
	v_fma_f32 v6, v18, v6, v12
	v_fma_f32 v7, v19, v7, v13
	v_fma_f32 v4, v16, v4, v10
	v_fma_f32 v5, v17, v5, v11
	v_mul_f32_e32 v12, v8, v0
	v_mul_f32_e32 v13, v9, v0
	v_cvt_pk_bf16_f32 v4, v4, v5
	v_cvt_pk_bf16_f32 v5, v6, v7
	global_store_dwordx2 v[2:3], v[4:5], off offset:3072
	ds_read_b128 v[4:7], v40 offset:39936
	ds_read_b128 v[8:11], v41 offset:7168
	s_waitcnt lgkmcnt(0)
	v_fma_f32 v6, v14, v6, v10
	v_fma_f32 v7, v15, v7, v11
	v_fma_f32 v4, v12, v4, v8
	v_fma_f32 v5, v13, v5, v9
	s_nop 0
	v_cvt_pk_bf16_f32 v4, v4, v5
	v_cvt_pk_bf16_f32 v5, v6, v7
	global_store_dwordx2 v[2:3], v[4:5], off offset:3584

; __device__ __forceinline__ f32x4 sigm4(f32x4 v) { const f32x4 t = v * -1.4426950408889634f; f32x4 e = {__builtin_amdgcn_exp2f(t[0]), __builtin_amdgcn_exp2f(t[1]), __builtin_amdgcn_exp2f(t[2]), __builtin_amdgcn_exp2f(t[3])};
;     e = e + 1.0f; return (f32x4){__builtin_amdgcn_rcpf(e[0]), __builtin_amdgcn_rcpf(e[1]), __builtin_amdgcn_rcpf(e[2]), __builtin_amdgcn_rcpf(e[3])}; }
;     __device__ __forceinline__ void operator()(const f32x4 (&acc)[2][2][4][2], const Unit& u, int wr, int wc, int fr_in, int fq_in) const {
;     ...
;                     if (type == 4) { v0 = sigm4(v0); v1 = sigm4(v1); }
.LBB0_311:
	v_mul_f32_e32 v2, s96, v146
	v_mul_f32_e32 v3, s96, v147
	v_mul_f32_e32 v144, s96, v144
	v_mul_f32_e32 v145, s96, v145
	v_exp_f32_e32 v2, v2
	v_exp_f32_e32 v3, v3
	v_mul_f32_e32 v140, s96, v140
	v_mul_f32_e32 v141, s96, v141
	v_exp_f32_e32 v144, v144
	v_exp_f32_e32 v145, v145
	v_add_f32_e32 v2, 1.0, v2
	v_add_f32_e32 v3, 1.0, v3
	v_exp_f32_e32 v140, v140
	v_rcp_f32_e32 v146, v2
	v_rcp_f32_e32 v147, v3
	v_mul_f32_e32 v2, s96, v142
	v_mul_f32_e32 v3, s96, v143
	v_exp_f32_e32 v141, v141
	v_exp_f32_e32 v2, v2
	v_exp_f32_e32 v3, v3
	v_add_f32_e32 v144, 1.0, v144
	v_add_f32_e32 v145, 1.0, v145
	v_add_f32_e32 v140, 1.0, v140
	v_add_f32_e32 v141, 1.0, v141
	v_rcp_f32_e32 v144, v144
	v_add_f32_e32 v2, 1.0, v2
	v_add_f32_e32 v3, 1.0, v3
	v_rcp_f32_e32 v145, v145
	v_rcp_f32_e32 v140, v140
	v_rcp_f32_e32 v141, v141
	v_rcp_f32_e32 v142, v2
	v_rcp_f32_e32 v143, v3

; __device__ __forceinline__ f32x4 sigm4(f32x4 v) { const f32x4 t = v * -1.4426950408889634f; f32x4 e = {__builtin_amdgcn_exp2f(t[0]), __builtin_amdgcn_exp2f(t[1]), __builtin_amdgcn_exp2f(t[2]), __builtin_amdgcn_exp2f(t[3])};
;     e = e + 1.0f; return (f32x4){__builtin_amdgcn_rcpf(e[0]), __builtin_amdgcn_rcpf(e[1]), __builtin_amdgcn_rcpf(e[2]), __builtin_amdgcn_rcpf(e[3])}; }
; __device__ __forceinline__ f32x4 silu4(f32x4 v) { return v * sigm4(v); }
;     __device__ __forceinline__ void operator()(const f32x4 (&acc)[2][2][4][2], const Unit& u, int wr, int wc, int fr_in, int fq_in) const {
;     ...
;                     if (type == 0) { v0 = silu4(v0); v1 = silu4(v1); }
;                     if (type == 4) { v0 = sigm4(v0); v1 = sigm4(v1); }
.LBB0_315:
	v_mul_f32_e32 v2, s96, v146
	v_mul_f32_e32 v3, s96, v147
	v_mul_f32_e32 v148, s96, v144
	v_mul_f32_e32 v149, s96, v145
	v_exp_f32_e32 v2, v2
	v_exp_f32_e32 v148, v148
	v_exp_f32_e32 v149, v149
	v_exp_f32_e32 v3, v3
	v_add_f32_e32 v148, 1.0, v148
	v_add_f32_e32 v149, 1.0, v149
	v_add_f32_e32 v2, 1.0, v2
	v_add_f32_e32 v3, 1.0, v3
	v_rcp_f32_e32 v148, v148
	v_rcp_f32_e32 v149, v149
	v_rcp_f32_e32 v2, v2
	v_rcp_f32_e32 v3, v3
	v_mul_f32_e32 v144, v144, v148
	v_mul_f32_e32 v145, v145, v149
	v_mul_f32_e32 v148, s96, v140
	v_mul_f32_e32 v149, s96, v141
	v_mul_f32_e32 v146, v146, v2
	v_mul_f32_e32 v147, v147, v3
	v_mul_f32_e32 v2, s96, v142
	v_mul_f32_e32 v3, s96, v143
	v_exp_f32_e32 v148, v148
	v_exp_f32_e32 v149, v149
	v_exp_f32_e32 v2, v2
	v_exp_f32_e32 v3, v3
	v_add_f32_e32 v148, 1.0, v148
	v_add_f32_e32 v149, 1.0, v149
	s_nop 0
	v_rcp_f32_e32 v148, v148
	v_add_f32_e32 v2, 1.0, v2
	v_add_f32_e32 v3, 1.0, v3
	v_rcp_f32_e32 v149, v149
	v_rcp_f32_e32 v2, v2
	v_rcp_f32_e32 v3, v3
	v_mul_f32_e32 v140, v140, v148
	v_mul_f32_e32 v141, v141, v149
	v_mul_f32_e32 v142, v142, v2
	v_mul_f32_e32 v143, v143, v3
	s_cmp_eq_u32 s7, 4
	s_cselect_b64 s[34:35], -1, 0
	s_cmp_lg_u32 s7, 4
	s_cbranch_scc0 .LBB0_311
	s_branch .LBB0_312

; __device__ __forceinline__ f32x4 silu4(f32x4 v) { return v * sigm4(v); }
; __device__ __forceinline__ u32x4 pack8(f32x4 v0, f32x4 v1) { u32x4 w; w.x = cvt_pk_bf16(v0[0], v0[1]); w.y = cvt_pk_bf16(v0[2], v0[3]); w.z = cvt_pk_bf16(v1[0], v1[1]); w.w = cvt_pk_bf16(v1[2], v1[3]); return w; }
; __device__ __forceinline__ void hg_gate4(f32x4& z, f32x4& key, const f32x4 l) {
;     const f32x4 zc = {__builtin_amdgcn_fmed3f(z[0], -80.f, 80.f), __builtin_amdgcn_fmed3f(z[1], -80.f, 80.f), __builtin_amdgcn_fmed3f(z[2], -80.f, 80.f), __builtin_amdgcn_fmed3f(z[3], -80.f, 80.f)};
;     const f32x4 t = zc * -1.4426950408889634f;
;     const f32x4 e = {__builtin_amdgcn_exp2f(t[0]), __builtin_amdgcn_exp2f(t[1]), __builtin_amdgcn_exp2f(t[2]), __builtin_amdgcn_exp2f(t[3])};
;     const f32x4 den = e + 1.0f;
;     const f32x4 sg = {__builtin_amdgcn_rcpf(den[0]), __builtin_amdgcn_rcpf(den[1]), __builtin_amdgcn_rcpf(den[2]), __builtin_amdgcn_rcpf(den[3])};
;     const f32x4 oml = 1.0f - l;
;     const f32x4 f = l + oml * sg;
;     z = (f32x4){__builtin_amdgcn_logf(f[0]), __builtin_amdgcn_logf(f[1]), __builtin_amdgcn_logf(f[2]), __builtin_amdgcn_logf(f[3])} * 0.6931471805599453f;
;     key = oml * (e * sg);
; }
;     __device__ __forceinline__ void operator()(const f32x4 (&acc)[2][2][4][2], const Unit& u, int wr, int wc, int fr_in, int fq_in) const {
;     ...
;                 for (int bj = 0; bj < 2; ++bj) {
;                     f32x4 v0 = acc[ai][bj][m][0], v1 = acc[ai][bj][m][1];
;                     if (type == 0) { v0 = silu4(v0); v1 = silu4(v1); }
;                     if (type == 4) { v0 = sigm4(v0); v1 = sigm4(v1); }
;                     if (type == 1 || type == 2) {
;                         f32x4 k0, k1;
;                         hg_gate4(v0, k0, lbv[bj][0]); hg_gate4(v1, k1, lbv[bj][1]);
;                         st16(base + tstride, roff + bj * HALF, pack8(k0, k1));
;                     }
;                     st16(base, roff + bj * HALF, pack8(v0, v1));
.LBB0_317:
	s_andn2_b64 vcc, exec, s[12:13]
	s_waitcnt vmcnt(0)
	v_sub_f32_e32 v153, 1.0, v49
	v_sub_f32_e32 v152, 1.0, v48
	v_sub_f32_e32 v155, 1.0, v51
	v_sub_f32_e32 v154, 1.0, v50
	v_sub_f32_e32 v149, 1.0, v37
	v_sub_f32_e32 v148, 1.0, v36
	v_sub_f32_e32 v151, 1.0, v39
	v_sub_f32_e32 v150, 1.0, v38
	s_cbranch_vccnz .LBB0_319
	v_med3_f32 v2, v144, s95, v182
	v_med3_f32 v3, v145, s95, v182
	v_med3_f32 v144, v146, s95, v182
	v_med3_f32 v145, v147, s95, v182
	v_mul_f32_e32 v144, s96, v144
	v_mul_f32_e32 v145, s96, v145
	v_mul_f32_e32 v2, s96, v2
	v_mul_f32_e32 v3, s96, v3
	v_exp_f32_e32 v170, v144
	v_exp_f32_e32 v2, v2
	v_exp_f32_e32 v171, v145
	v_exp_f32_e32 v3, v3
	v_med3_f32 v140, v140, s95, v182
	v_med3_f32 v141, v141, s95, v182
	v_add_f32_e32 v144, 1.0, v170
	v_add_f32_e32 v145, 1.0, v171
	v_add_f32_e32 v146, 1.0, v2
	v_add_f32_e32 v147, 1.0, v3
	v_rcp_f32_e32 v174, v144
	v_rcp_f32_e32 v172, v146
	v_rcp_f32_e32 v175, v145
	v_rcp_f32_e32 v173, v147
	v_mul_f32_e32 v140, s96, v140
	v_mul_f32_e32 v141, s96, v141
	v_med3_f32 v142, v142, s95, v182
	v_fma_f32 v144, v154, v174, v50
	v_fma_f32 v145, v155, v175, v51
	v_fma_f32 v146, v152, v172, v48
	v_fma_f32 v147, v153, v173, v49
	v_exp_f32_e32 v178, v140
	v_exp_f32_e32 v179, v141
	v_log_f32_e32 v176, v146
	v_log_f32_e32 v177, v147
	v_log_f32_e32 v144, v144
	v_log_f32_e32 v145, v145
	v_med3_f32 v143, v143, s95, v182
	v_mul_f32_e32 v142, s96, v142
	v_mul_f32_e32 v143, s96, v143
	v_mul_f32_e32 v2, v2, v172
	v_mul_f32_e32 v3, v3, v173
	v_exp_f32_e32 v180, v142
	v_exp_f32_e32 v181, v143
	v_add_f32_e32 v142, 1.0, v178
	v_add_f32_e32 v143, 1.0, v179
	v_mul_f32_e32 v146, s68, v144
	v_mul_f32_e32 v147, s68, v145
	v_mul_f32_e32 v144, s68, v176
	v_mul_f32_e32 v145, s68, v177
	v_rcp_f32_e32 v176, v142
	v_rcp_f32_e32 v177, v143
	v_add_f32_e32 v140, 1.0, v180
	v_add_f32_e32 v141, 1.0, v181
	v_mul_f32_e32 v2, v152, v2
	v_mul_f32_e32 v3, v153, v3
	v_rcp_f32_e32 v184, v140
	v_rcp_f32_e32 v185, v141
	v_mul_f32_e32 v140, v170, v174
	v_mul_f32_e32 v141, v171, v175
	v_fma_f32 v170, v148, v176, v36
	v_fma_f32 v171, v149, v177, v37
	v_mul_f32_e32 v172, v154, v140
	v_mul_f32_e32 v173, v155, v141
	v_log_f32_e32 v170, v170
	v_log_f32_e32 v171, v171
	v_fma_f32 v142, v150, v184, v38
	v_fma_f32 v143, v151, v185, v39
	v_mul_f32_e32 v174, v180, v184
	v_mul_f32_e32 v175, v181, v185
	v_log_f32_e32 v142, v142
	v_log_f32_e32 v143, v143
	v_mul_f32_e32 v140, s68, v170
	v_mul_f32_e32 v141, s68, v171
	v_mul_f32_e32 v170, v178, v176
	v_mul_f32_e32 v171, v179, v177
	v_mul_f32_e32 v174, v150, v174
	v_mul_f32_e32 v175, v151, v175
	v_mul_f32_e32 v176, v148, v170
	v_mul_f32_e32 v177, v149, v171
	v_cvt_pk_bf16_f32 v170, v2, v3
	v_lshl_add_u64 v[2:3], s[30:31], 0, v[0:1]
	v_add_co_u32_e32 v2, vcc, 0x4400000, v2
	v_mul_f32_e32 v142, s68, v142
	v_mul_f32_e32 v143, s68, v143
	s_nop 0
	v_addc_co_u32_e32 v3, vcc, 0, v3, vcc
	v_cvt_pk_bf16_f32 v171, v172, v173
	v_cvt_pk_bf16_f32 v172, v176, v177
	v_cvt_pk_bf16_f32 v173, v174, v175
	global_store_dwordx4 v[2:3], v[170:173], off
.LBB0_319:
	v_lshl_add_u64 v[2:3], s[30:31], 0, v[0:1]
	s_and_b64 vcc, exec, s[8:9]
	v_cvt_pk_bf16_f32 v144, v144, v145
	v_cvt_pk_bf16_f32 v145, v146, v147
	v_cvt_pk_bf16_f32 v146, v140, v141
	v_cvt_pk_bf16_f32 v147, v142, v143
	global_store_dwordx4 v[2:3], v[144:147], off
	s_cbranch_vccnz .LBB0_331
	v_mul_f32_e32 v2, s96, v138
	v_mul_f32_e32 v3, s96, v139
	v_mul_f32_e32 v140, s96, v136
	v_mul_f32_e32 v141, s96, v137
	v_exp_f32_e32 v2, v2
	v_exp_f32_e32 v140, v140
	v_exp_f32_e32 v141, v141
	v_exp_f32_e32 v3, v3
	v_add_f32_e32 v140, 1.0, v140
	v_add_f32_e32 v141, 1.0, v141
	v_add_f32_e32 v2, 1.0, v2
	v_add_f32_e32 v3, 1.0, v3
	v_rcp_f32_e32 v140, v140
	v_rcp_f32_e32 v141, v141
	v_rcp_f32_e32 v2, v2
	v_rcp_f32_e32 v3, v3
	v_mul_f32_e32 v136, v136, v140
	v_mul_f32_e32 v137, v137, v141
	v_mul_f32_e32 v140, s96, v132
	v_mul_f32_e32 v141, s96, v133
	v_mul_f32_e32 v138, v138, v2
	v_mul_f32_e32 v139, v139, v3
	v_mul_f32_e32 v2, s96, v134
	v_mul_f32_e32 v3, s96, v135
	v_exp_f32_e32 v140, v140
	v_exp_f32_e32 v141, v141
	v_exp_f32_e32 v2, v2
	v_exp_f32_e32 v3, v3
	v_add_f32_e32 v140, 1.0, v140
	v_add_f32_e32 v141, 1.0, v141
	s_nop 0
	v_rcp_f32_e32 v140, v140
	v_add_f32_e32 v2, 1.0, v2
	v_add_f32_e32 v3, 1.0, v3
	v_rcp_f32_e32 v141, v141
	v_rcp_f32_e32 v2, v2
	v_rcp_f32_e32 v3, v3
	v_mul_f32_e32 v132, v132, v140
	v_mul_f32_e32 v133, v133, v141
	v_mul_f32_e32 v134, v134, v2
	v_mul_f32_e32 v135, v135, v3
	v_cndmask_b32_e64 v2, 0, 1, s[34:35]
	v_cmp_ne_u32_e64 s[12:13], 1, v2
	s_andn2_b64 vcc, exec, s[34:35]
	s_cbranch_vccz .LBB0_332

; __device__ __forceinline__ f32x4 silu4(f32x4 v) { return v * sigm4(v); }
; __device__ __forceinline__ u32x4 pack8(f32x4 v0, f32x4 v1) { u32x4 w; w.x = cvt_pk_bf16(v0[0], v0[1]); w.y = cvt_pk_bf16(v0[2], v0[3]); w.z = cvt_pk_bf16(v1[0], v1[1]); w.w = cvt_pk_bf16(v1[2], v1[3]); return w; }
; __device__ __forceinline__ void hg_gate4(f32x4& z, f32x4& key, const f32x4 l) {
;     const f32x4 zc = {__builtin_amdgcn_fmed3f(z[0], -80.f, 80.f), __builtin_amdgcn_fmed3f(z[1], -80.f, 80.f), __builtin_amdgcn_fmed3f(z[2], -80.f, 80.f), __builtin_amdgcn_fmed3f(z[3], -80.f, 80.f)};
;     const f32x4 t = zc * -1.4426950408889634f;
;     const f32x4 e = {__builtin_amdgcn_exp2f(t[0]), __builtin_amdgcn_exp2f(t[1]), __builtin_amdgcn_exp2f(t[2]), __builtin_amdgcn_exp2f(t[3])};
;     const f32x4 den = e + 1.0f;
;     const f32x4 sg = {__builtin_amdgcn_rcpf(den[0]), __builtin_amdgcn_rcpf(den[1]), __builtin_amdgcn_rcpf(den[2]), __builtin_amdgcn_rcpf(den[3])};
;     const f32x4 oml = 1.0f - l;
;     const f32x4 f = l + oml * sg;
;     z = (f32x4){__builtin_amdgcn_logf(f[0]), __builtin_amdgcn_logf(f[1]), __builtin_amdgcn_logf(f[2]), __builtin_amdgcn_logf(f[3])} * 0.6931471805599453f;
;     key = oml * (e * sg);
; }
;     __device__ __forceinline__ void operator()(const f32x4 (&acc)[2][2][4][2], const Unit& u, int wr, int wc, int fr_in, int fq_in) const {
;     ...
;                 for (int bj = 0; bj < 2; ++bj) {
;                     f32x4 v0 = acc[ai][bj][m][0], v1 = acc[ai][bj][m][1];
;                     if (type == 0) { v0 = silu4(v0); v1 = silu4(v1); }
;                     if (type == 4) { v0 = sigm4(v0); v1 = sigm4(v1); }
;                     if (type == 1 || type == 2) {
;                         f32x4 k0, k1;
;                         hg_gate4(v0, k0, lbv[bj][0]); hg_gate4(v1, k1, lbv[bj][1]);
;                         st16(base + tstride, roff + bj * HALF, pack8(k0, k1));
;                     }
;                     st16(base, roff + bj * HALF, pack8(v0, v1));
.LBB0_323:
	s_andn2_b64 vcc, exec, s[34:35]
	v_sub_f32_e32 v143, 1.0, v25
	v_sub_f32_e32 v142, 1.0, v24
	v_sub_f32_e32 v145, 1.0, v27
	v_sub_f32_e32 v144, 1.0, v26
	v_sub_f32_e32 v3, 1.0, v21
	v_sub_f32_e32 v2, 1.0, v20
	v_sub_f32_e32 v141, 1.0, v23
	v_sub_f32_e32 v140, 1.0, v22
	s_cbranch_vccnz .LBB0_325
	v_med3_f32 v136, v136, s95, v182
	v_med3_f32 v137, v137, s95, v182
	v_med3_f32 v138, v138, s95, v182
	v_med3_f32 v139, v139, s95, v182
	v_mul_f32_e32 v138, s96, v138
	v_mul_f32_e32 v139, s96, v139
	v_mul_f32_e32 v136, s96, v136
	v_mul_f32_e32 v137, s96, v137
	v_exp_f32_e32 v170, v138
	v_exp_f32_e32 v146, v136
	v_exp_f32_e32 v171, v139
	v_exp_f32_e32 v147, v137
	v_med3_f32 v134, v134, s95, v182
	v_med3_f32 v135, v135, s95, v182
	v_add_f32_e32 v136, 1.0, v170
	v_add_f32_e32 v137, 1.0, v171
	v_add_f32_e32 v138, 1.0, v146
	v_add_f32_e32 v139, 1.0, v147
	v_rcp_f32_e32 v174, v136
	v_rcp_f32_e32 v172, v138
	v_rcp_f32_e32 v175, v137
	v_rcp_f32_e32 v173, v139
	v_med3_f32 v132, v132, s95, v182
	v_med3_f32 v133, v133, s95, v182
	v_mul_f32_e32 v134, s96, v134
	v_mul_f32_e32 v135, s96, v135
	v_mul_f32_e32 v132, s96, v132
	v_mul_f32_e32 v133, s96, v133
	v_exp_f32_e32 v180, v134
	v_exp_f32_e32 v181, v135
	v_fma_f32 v136, v144, v174, v26
	v_fma_f32 v137, v145, v175, v27
	v_fma_f32 v138, v142, v172, v24
	v_fma_f32 v139, v143, v173, v25
	v_exp_f32_e32 v178, v132
	v_exp_f32_e32 v179, v133
	v_log_f32_e32 v176, v138
	v_log_f32_e32 v177, v139
	v_log_f32_e32 v136, v136
	v_log_f32_e32 v137, v137
	v_add_f32_e32 v132, 1.0, v180
	v_add_f32_e32 v133, 1.0, v181
	v_add_f32_e32 v134, 1.0, v178
	v_add_f32_e32 v135, 1.0, v179
	v_rcp_f32_e32 v184, v132
	v_rcp_f32_e32 v185, v133
	v_mul_f32_e32 v138, s68, v136
	v_mul_f32_e32 v139, s68, v137
	v_mul_f32_e32 v136, s68, v176
	v_mul_f32_e32 v137, s68, v177
	v_rcp_f32_e32 v176, v134
	v_rcp_f32_e32 v177, v135
	v_mul_f32_e32 v132, v146, v172
	v_mul_f32_e32 v133, v147, v173
	v_fma_f32 v146, v140, v184, v22
	v_fma_f32 v147, v141, v185, v23
	v_mul_f32_e32 v134, v170, v174
	v_mul_f32_e32 v135, v171, v175
	v_fma_f32 v170, v2, v176, v20
	v_fma_f32 v171, v3, v177, v21
	v_log_f32_e32 v146, v146
	v_log_f32_e32 v147, v147
	v_log_f32_e32 v170, v170
	v_log_f32_e32 v171, v171
	v_mul_f32_e32 v172, v144, v134
	v_mul_f32_e32 v173, v145, v135
	v_mul_f32_e32 v134, s68, v146
	v_mul_f32_e32 v135, s68, v147
	v_mul_f32_e32 v146, v178, v176
	v_mul_f32_e32 v147, v179, v177
	v_mul_f32_e32 v174, v142, v132
	v_mul_f32_e32 v175, v143, v133
	v_mul_f32_e32 v132, s68, v170
	v_mul_f32_e32 v133, s68, v171
	v_mul_f32_e32 v170, v180, v184
	v_mul_f32_e32 v171, v181, v185
	v_mul_f32_e32 v146, v2, v146
	v_mul_f32_e32 v147, v3, v147
	v_mul_f32_e32 v176, v140, v170
	v_mul_f32_e32 v177, v141, v171
	v_cvt_pk_bf16_f32 v170, v174, v175
	v_cvt_pk_bf16_f32 v171, v172, v173
	v_cvt_pk_bf16_f32 v172, v146, v147
	v_lshl_add_u64 v[146:147], s[30:31], 0, v[0:1]
	v_add_co_u32_e32 v146, vcc, 0x4400000, v146
	v_cvt_pk_bf16_f32 v173, v176, v177
	s_nop 1
	v_addc_co_u32_e32 v147, vcc, 0, v147, vcc
	global_store_dwordx4 v[146:147], v[170:173], off
.LBB0_325:
	v_cvt_pk_bf16_f32 v136, v136, v137
	v_cvt_pk_bf16_f32 v137, v138, v139
	v_cvt_pk_bf16_f32 v138, v132, v133
	v_lshl_add_u64 v[132:133], s[30:31], 0, v[0:1]
	s_and_b64 vcc, exec, s[8:9]
	v_cvt_pk_bf16_f32 v139, v134, v135
	global_store_dwordx4 v[132:133], v[136:139], off
	s_cbranch_vccnz .LBB0_327
	v_mul_f32_e32 v132, s96, v130
	v_mul_f32_e32 v133, s96, v131
	v_mul_f32_e32 v134, s96, v128
	v_mul_f32_e32 v135, s96, v129
	v_exp_f32_e32 v132, v132
	v_exp_f32_e32 v134, v134
	v_exp_f32_e32 v135, v135
	v_exp_f32_e32 v133, v133
	v_add_f32_e32 v134, 1.0, v134
	v_add_f32_e32 v135, 1.0, v135
	v_add_f32_e32 v132, 1.0, v132
	v_add_f32_e32 v133, 1.0, v133
	v_rcp_f32_e32 v134, v134
	v_rcp_f32_e32 v135, v135
	v_rcp_f32_e32 v132, v132
	v_rcp_f32_e32 v133, v133
	v_mul_f32_e32 v128, v128, v134
	v_mul_f32_e32 v129, v129, v135
	v_mul_f32_e32 v134, s96, v124
	v_mul_f32_e32 v135, s96, v125
	v_mul_f32_e32 v130, v130, v132
	v_mul_f32_e32 v131, v131, v133
	v_mul_f32_e32 v132, s96, v126
	v_mul_f32_e32 v133, s96, v127
	v_exp_f32_e32 v134, v134
	v_exp_f32_e32 v135, v135
	v_exp_f32_e32 v132, v132
	v_exp_f32_e32 v133, v133
	v_add_f32_e32 v134, 1.0, v134
	v_add_f32_e32 v135, 1.0, v135
	s_nop 0
	v_rcp_f32_e32 v134, v134
	v_add_f32_e32 v132, 1.0, v132
	v_add_f32_e32 v133, 1.0, v133
	v_rcp_f32_e32 v135, v135
	v_rcp_f32_e32 v132, v132
	v_rcp_f32_e32 v133, v133
	v_mul_f32_e32 v124, v124, v134
	v_mul_f32_e32 v125, v125, v135
	v_mul_f32_e32 v126, v126, v132
	v_mul_f32_e32 v127, v127, v133
.LBB0_327:
	s_and_b64 vcc, exec, s[12:13]
	s_cbranch_vccnz .LBB0_329
	v_mul_f32_e32 v130, s96, v130
	v_mul_f32_e32 v131, s96, v131
	v_mul_f32_e32 v128, s96, v128
	v_mul_f32_e32 v129, s96, v129
	v_mul_f32_e32 v126, s96, v126
	v_mul_f32_e32 v127, s96, v127
	v_mul_f32_e32 v124, s96, v124
	v_mul_f32_e32 v125, s96, v125
	v_exp_f32_e32 v128, v128
	v_exp_f32_e32 v129, v129
	v_exp_f32_e32 v130, v130
	v_exp_f32_e32 v131, v131
	v_exp_f32_e32 v124, v124
	v_exp_f32_e32 v125, v125
	v_exp_f32_e32 v126, v126
	v_exp_f32_e32 v127, v127
	v_add_f32_e32 v130, 1.0, v130
	v_add_f32_e32 v131, 1.0, v131
	v_add_f32_e32 v128, 1.0, v128
	v_add_f32_e32 v129, 1.0, v129
	v_add_f32_e32 v124, 1.0, v124
	v_add_f32_e32 v125, 1.0, v125
	v_add_f32_e32 v126, 1.0, v126
	v_add_f32_e32 v127, 1.0, v127
	v_rcp_f32_e32 v128, v128
	v_rcp_f32_e32 v129, v129
	v_rcp_f32_e32 v130, v130
	v_rcp_f32_e32 v131, v131
	v_rcp_f32_e32 v124, v124
	v_rcp_f32_e32 v125, v125
	v_rcp_f32_e32 v126, v126
	v_rcp_f32_e32 v127, v127

; __device__ __forceinline__ f32x4 silu4(f32x4 v) { return v * sigm4(v); }
; __device__ __forceinline__ u32x4 pack8(f32x4 v0, f32x4 v1) { u32x4 w; w.x = cvt_pk_bf16(v0[0], v0[1]); w.y = cvt_pk_bf16(v0[2], v0[3]); w.z = cvt_pk_bf16(v1[0], v1[1]); w.w = cvt_pk_bf16(v1[2], v1[3]); return w; }
; __device__ __forceinline__ void hg_gate4(f32x4& z, f32x4& key, const f32x4 l) {
;     const f32x4 zc = {__builtin_amdgcn_fmed3f(z[0], -80.f, 80.f), __builtin_amdgcn_fmed3f(z[1], -80.f, 80.f), __builtin_amdgcn_fmed3f(z[2], -80.f, 80.f), __builtin_amdgcn_fmed3f(z[3], -80.f, 80.f)};
;     const f32x4 t = zc * -1.4426950408889634f;
;     const f32x4 e = {__builtin_amdgcn_exp2f(t[0]), __builtin_amdgcn_exp2f(t[1]), __builtin_amdgcn_exp2f(t[2]), __builtin_amdgcn_exp2f(t[3])};
;     const f32x4 den = e + 1.0f;
;     const f32x4 sg = {__builtin_amdgcn_rcpf(den[0]), __builtin_amdgcn_rcpf(den[1]), __builtin_amdgcn_rcpf(den[2]), __builtin_amdgcn_rcpf(den[3])};
;     const f32x4 oml = 1.0f - l;
;     const f32x4 f = l + oml * sg;
;     z = (f32x4){__builtin_amdgcn_logf(f[0]), __builtin_amdgcn_logf(f[1]), __builtin_amdgcn_logf(f[2]), __builtin_amdgcn_logf(f[3])} * 0.6931471805599453f;
;     key = oml * (e * sg);
; }
;     __device__ __forceinline__ void operator()(const f32x4 (&acc)[2][2][4][2], const Unit& u, int wr, int wc, int fr_in, int fq_in) const {
;     ...
;                 for (int bj = 0; bj < 2; ++bj) {
;                     f32x4 v0 = acc[ai][bj][m][0], v1 = acc[ai][bj][m][1];
;                     if (type == 0) { v0 = silu4(v0); v1 = silu4(v1); }
;                     if (type == 4) { v0 = sigm4(v0); v1 = sigm4(v1); }
;                     if (type == 1 || type == 2) {
;                         f32x4 k0, k1;
;                         hg_gate4(v0, k0, lbv[bj][0]); hg_gate4(v1, k1, lbv[bj][1]);
;                         st16(base + tstride, roff + bj * HALF, pack8(k0, k1));
;                     }
;                     st16(base, roff + bj * HALF, pack8(v0, v1));
.LBB0_332:
	v_mul_f32_e32 v2, s96, v138
	v_mul_f32_e32 v3, s96, v139
	v_mul_f32_e32 v136, s96, v136
	v_mul_f32_e32 v137, s96, v137
	v_exp_f32_e32 v2, v2
	v_exp_f32_e32 v3, v3
	v_mul_f32_e32 v132, s96, v132
	v_mul_f32_e32 v133, s96, v133
	v_exp_f32_e32 v136, v136
	v_exp_f32_e32 v137, v137
	v_add_f32_e32 v2, 1.0, v2
	v_add_f32_e32 v3, 1.0, v3
	v_exp_f32_e32 v132, v132
	v_rcp_f32_e32 v138, v2
	v_rcp_f32_e32 v139, v3
	v_mul_f32_e32 v2, s96, v134
	v_mul_f32_e32 v3, s96, v135
	v_exp_f32_e32 v133, v133
	v_exp_f32_e32 v2, v2
	v_exp_f32_e32 v3, v3
	v_add_f32_e32 v136, 1.0, v136
	v_add_f32_e32 v137, 1.0, v137
	v_add_f32_e32 v132, 1.0, v132
	v_add_f32_e32 v133, 1.0, v133
	v_rcp_f32_e32 v136, v136
	v_add_f32_e32 v2, 1.0, v2
	v_add_f32_e32 v3, 1.0, v3
	v_rcp_f32_e32 v137, v137
	v_rcp_f32_e32 v132, v132
	v_rcp_f32_e32 v133, v133
	v_rcp_f32_e32 v134, v2
	v_rcp_f32_e32 v135, v3
	s_mov_b64 s[34:35], -1
	s_and_b64 vcc, exec, s[10:11]
	v_add_u32_e32 v0, 0x100, v0
	s_cbranch_vccz .LBB0_322
	s_branch .LBB0_323
.LBB0_333:
.LBB0_334:
	v_med3_f32 v128, v128, s95, v182
	v_med3_f32 v129, v129, s95, v182
	v_med3_f32 v130, v130, s95, v182
	v_med3_f32 v131, v131, s95, v182
	v_mul_f32_e32 v130, s96, v130
	v_mul_f32_e32 v131, s96, v131
	v_mul_f32_e32 v128, s96, v128
	v_mul_f32_e32 v129, s96, v129
	v_exp_f32_e32 v136, v130
	v_exp_f32_e32 v134, v128
	v_exp_f32_e32 v137, v131
	v_exp_f32_e32 v135, v129
	v_med3_f32 v124, v124, s95, v182
	v_med3_f32 v125, v125, s95, v182
	v_add_f32_e32 v128, 1.0, v136
	v_add_f32_e32 v129, 1.0, v137
	v_add_f32_e32 v130, 1.0, v134
	v_add_f32_e32 v131, 1.0, v135
	v_rcp_f32_e32 v146, v128
	v_rcp_f32_e32 v138, v130
	v_rcp_f32_e32 v147, v129
	v_rcp_f32_e32 v139, v131
	v_med3_f32 v126, v126, s95, v182
	v_med3_f32 v127, v127, s95, v182
	v_mul_f32_e32 v126, s96, v126
	v_mul_f32_e32 v127, s96, v127
	v_mul_f32_e32 v124, s96, v124
	v_mul_f32_e32 v125, s96, v125
	v_fma_f32 v128, v154, v146, v50
	v_fma_f32 v129, v155, v147, v51
	v_fma_f32 v130, v152, v138, v48
	v_fma_f32 v131, v153, v139, v49
	v_exp_f32_e32 v170, v124
	v_exp_f32_e32 v172, v126
	v_exp_f32_e32 v173, v127
	v_exp_f32_e32 v171, v125
	v_log_f32_e32 v156, v130
	v_log_f32_e32 v157, v131
	v_log_f32_e32 v128, v128
	v_log_f32_e32 v129, v129
	v_add_f32_e32 v124, 1.0, v172
	v_add_f32_e32 v125, 1.0, v173
	v_add_f32_e32 v126, 1.0, v170
	v_add_f32_e32 v127, 1.0, v171
	v_rcp_f32_e32 v174, v124
	v_mul_f32_e32 v130, s68, v128
	v_mul_f32_e32 v131, s68, v129
	v_mul_f32_e32 v128, s68, v156
	v_mul_f32_e32 v129, s68, v157
	v_rcp_f32_e32 v156, v126
	v_rcp_f32_e32 v175, v125
	v_rcp_f32_e32 v157, v127
	v_mul_f32_e32 v124, v134, v138
	v_mul_f32_e32 v125, v135, v139
	v_mul_f32_e32 v126, v136, v146
	v_mul_f32_e32 v127, v137, v147
	v_fma_f32 v134, v150, v174, v38
	v_fma_f32 v135, v151, v175, v39
	v_fma_f32 v136, v148, v156, v36
	v_fma_f32 v137, v149, v157, v37
	v_log_f32_e32 v134, v134
	v_log_f32_e32 v136, v136
	v_log_f32_e32 v135, v135
	v_log_f32_e32 v137, v137
	v_mul_f32_e32 v138, v154, v126
	v_mul_f32_e32 v139, v155, v127
	v_mul_f32_e32 v146, v152, v124
	v_mul_f32_e32 v147, v153, v125
	v_mul_f32_e32 v126, s68, v134
	v_mul_f32_e32 v127, s68, v135
	v_mul_f32_e32 v124, s68, v136
	v_mul_f32_e32 v125, s68, v137
	v_mul_f32_e32 v134, v170, v156
	v_mul_f32_e32 v135, v171, v157
	v_mul_f32_e32 v136, v172, v174
	v_mul_f32_e32 v137, v173, v175
	s_nop 0
	v_mul_f32_e32 v156, v150, v136
	v_mul_f32_e32 v157, v151, v137
	v_mul_f32_e32 v136, v148, v134
	v_mul_f32_e32 v137, v149, v135
	v_cvt_pk_bf16_f32 v134, v146, v147
	v_cvt_pk_bf16_f32 v135, v138, v139
	v_lshl_add_u64 v[138:139], s[30:31], 0, v[0:1]
	v_add_co_u32_e32 v138, vcc, 0x4400000, v138
	v_cvt_pk_bf16_f32 v136, v136, v137
	v_cvt_pk_bf16_f32 v137, v156, v157
	s_nop 1
	v_addc_co_u32_e32 v139, vcc, 0, v139, vcc
	global_store_dwordx4 v[138:139], v[134:137], off
.LBB0_335:
	v_cvt_pk_bf16_f32 v128, v128, v129
	v_cvt_pk_bf16_f32 v129, v130, v131
	v_cvt_pk_bf16_f32 v130, v124, v125
	v_lshl_add_u64 v[124:125], s[30:31], 0, v[0:1]
	s_and_b64 vcc, exec, s[8:9]
	v_cvt_pk_bf16_f32 v131, v126, v127
	global_store_dwordx4 v[124:125], v[128:131], off
	s_cbranch_vccnz .LBB0_339
	v_mul_f32_e32 v124, s96, v122
	v_mul_f32_e32 v125, s96, v123
	v_mul_f32_e32 v126, s96, v120
	v_mul_f32_e32 v127, s96, v121
	v_exp_f32_e32 v124, v124
	v_exp_f32_e32 v126, v126
	v_exp_f32_e32 v127, v127
	v_exp_f32_e32 v125, v125
	v_add_f32_e32 v126, 1.0, v126
	v_add_f32_e32 v127, 1.0, v127
	v_add_f32_e32 v124, 1.0, v124
	v_add_f32_e32 v125, 1.0, v125
	v_rcp_f32_e32 v126, v126
	v_rcp_f32_e32 v127, v127
	v_rcp_f32_e32 v124, v124
	v_rcp_f32_e32 v125, v125
	v_mul_f32_e32 v120, v120, v126
	v_mul_f32_e32 v121, v121, v127
	v_mul_f32_e32 v126, s96, v116
	v_mul_f32_e32 v127, s96, v117
	v_mul_f32_e32 v122, v122, v124
	v_mul_f32_e32 v123, v123, v125
	v_mul_f32_e32 v124, s96, v118
	v_mul_f32_e32 v125, s96, v119
	v_exp_f32_e32 v126, v126
	v_exp_f32_e32 v127, v127
	v_exp_f32_e32 v124, v124
	v_exp_f32_e32 v125, v125
	v_add_f32_e32 v126, 1.0, v126
	v_add_f32_e32 v127, 1.0, v127
	s_nop 0
	v_rcp_f32_e32 v126, v126
	v_add_f32_e32 v124, 1.0, v124
	v_add_f32_e32 v125, 1.0, v125
	v_rcp_f32_e32 v127, v127
	v_rcp_f32_e32 v124, v124
	v_rcp_f32_e32 v125, v125
	v_mul_f32_e32 v116, v116, v126
	v_mul_f32_e32 v117, v117, v127
	v_mul_f32_e32 v118, v118, v124
	v_mul_f32_e32 v119, v119, v125
	s_and_b64 vcc, exec, s[12:13]
	s_cbranch_vccz .LBB0_340

; __device__ __forceinline__ f32x4 sigm4(f32x4 v) { const f32x4 t = v * -1.4426950408889634f; f32x4 e = {__builtin_amdgcn_exp2f(t[0]), __builtin_amdgcn_exp2f(t[1]), __builtin_amdgcn_exp2f(t[2]), __builtin_amdgcn_exp2f(t[3])};
;     e = e + 1.0f; return (f32x4){__builtin_amdgcn_rcpf(e[0]), __builtin_amdgcn_rcpf(e[1]), __builtin_amdgcn_rcpf(e[2]), __builtin_amdgcn_rcpf(e[3])}; }
;     __device__ __forceinline__ void operator()(const f32x4 (&acc)[2][2][4][2], const Unit& u, int wr, int wc, int fr_in, int fq_in) const {
;     ...
;                     if (type == 4) { v0 = sigm4(v0); v1 = sigm4(v1); }
.LBB0_340:
	v_mul_f32_e32 v122, s96, v122
	v_mul_f32_e32 v123, s96, v123
	v_mul_f32_e32 v120, s96, v120
	v_mul_f32_e32 v121, s96, v121
	v_mul_f32_e32 v118, s96, v118
	v_mul_f32_e32 v119, s96, v119
	v_mul_f32_e32 v116, s96, v116
	v_mul_f32_e32 v117, s96, v117
	v_exp_f32_e32 v120, v120
	v_exp_f32_e32 v121, v121
	v_exp_f32_e32 v122, v122
	v_exp_f32_e32 v123, v123
	v_exp_f32_e32 v116, v116
	v_exp_f32_e32 v117, v117
	v_exp_f32_e32 v118, v118
	v_exp_f32_e32 v119, v119
	v_add_f32_e32 v122, 1.0, v122
	v_add_f32_e32 v123, 1.0, v123
	v_add_f32_e32 v120, 1.0, v120
	v_add_f32_e32 v121, 1.0, v121
	v_add_f32_e32 v116, 1.0, v116
	v_add_f32_e32 v117, 1.0, v117
	v_add_f32_e32 v118, 1.0, v118
	v_add_f32_e32 v119, 1.0, v119
	v_rcp_f32_e32 v120, v120
	v_rcp_f32_e32 v121, v121
	v_rcp_f32_e32 v122, v122
	v_rcp_f32_e32 v123, v123
	v_rcp_f32_e32 v116, v116
	v_rcp_f32_e32 v117, v117
	v_rcp_f32_e32 v118, v118
	v_rcp_f32_e32 v119, v119
	s_mov_b64 s[34:35], -1
	s_and_b64 vcc, exec, s[10:11]
	v_add_u32_e32 v0, 0x100, v0
	s_cbranch_vccz .LBB0_338

; __device__ __forceinline__ u32x4 pack8(f32x4 v0, f32x4 v1) { u32x4 w; w.x = cvt_pk_bf16(v0[0], v0[1]); w.y = cvt_pk_bf16(v0[2], v0[3]); w.z = cvt_pk_bf16(v1[0], v1[1]); w.w = cvt_pk_bf16(v1[2], v1[3]); return w; }
; __device__ __forceinline__ void hg_gate4(f32x4& z, f32x4& key, const f32x4 l) {
;     const f32x4 zc = {__builtin_amdgcn_fmed3f(z[0], -80.f, 80.f), __builtin_amdgcn_fmed3f(z[1], -80.f, 80.f), __builtin_amdgcn_fmed3f(z[2], -80.f, 80.f), __builtin_amdgcn_fmed3f(z[3], -80.f, 80.f)};
;     const f32x4 t = zc * -1.4426950408889634f;
;     const f32x4 e = {__builtin_amdgcn_exp2f(t[0]), __builtin_amdgcn_exp2f(t[1]), __builtin_amdgcn_exp2f(t[2]), __builtin_amdgcn_exp2f(t[3])};
;     const f32x4 den = e + 1.0f;
;     const f32x4 sg = {__builtin_amdgcn_rcpf(den[0]), __builtin_amdgcn_rcpf(den[1]), __builtin_amdgcn_rcpf(den[2]), __builtin_amdgcn_rcpf(den[3])};
;     const f32x4 oml = 1.0f - l;
;     const f32x4 f = l + oml * sg;
;     z = (f32x4){__builtin_amdgcn_logf(f[0]), __builtin_amdgcn_logf(f[1]), __builtin_amdgcn_logf(f[2]), __builtin_amdgcn_logf(f[3])} * 0.6931471805599453f;
;     key = oml * (e * sg);
; }
;     __device__ __forceinline__ void operator()(const f32x4 (&acc)[2][2][4][2], const Unit& u, int wr, int wc, int fr_in, int fq_in) const {
;     ...
;                     if (type == 1 || type == 2) {
;                         f32x4 k0, k1;
;                         hg_gate4(v0, k0, lbv[bj][0]); hg_gate4(v1, k1, lbv[bj][1]);
;                         st16(base + tstride, roff + bj * HALF, pack8(k0, k1));
;                     }
;                     st16(base, roff + bj * HALF, pack8(v0, v1));
.LBB0_342:
	v_med3_f32 v120, v120, s95, v182
	v_med3_f32 v121, v121, s95, v182
	v_med3_f32 v122, v122, s95, v182
	v_med3_f32 v123, v123, s95, v182
	v_mul_f32_e32 v122, s96, v122
	v_mul_f32_e32 v123, s96, v123
	v_mul_f32_e32 v120, s96, v120
	v_mul_f32_e32 v121, s96, v121
	v_exp_f32_e32 v126, v122
	v_exp_f32_e32 v124, v120
	v_exp_f32_e32 v127, v123
	v_exp_f32_e32 v125, v121
	v_med3_f32 v116, v116, s95, v182
	v_med3_f32 v117, v117, s95, v182
	v_add_f32_e32 v120, 1.0, v126
	v_add_f32_e32 v121, 1.0, v127
	v_add_f32_e32 v122, 1.0, v124
	v_add_f32_e32 v123, 1.0, v125
	v_rcp_f32_e32 v130, v120
	v_rcp_f32_e32 v128, v122
	v_rcp_f32_e32 v131, v121
	v_rcp_f32_e32 v129, v123
	v_med3_f32 v118, v118, s95, v182
	v_med3_f32 v119, v119, s95, v182
	v_mul_f32_e32 v118, s96, v118
	v_mul_f32_e32 v119, s96, v119
	v_mul_f32_e32 v116, s96, v116
	v_mul_f32_e32 v117, s96, v117
	v_fma_f32 v120, v144, v130, v26
	v_fma_f32 v121, v145, v131, v27
	v_fma_f32 v122, v142, v128, v24
	v_fma_f32 v123, v143, v129, v25
	v_exp_f32_e32 v136, v116
	v_exp_f32_e32 v138, v118
	v_exp_f32_e32 v139, v119
	v_exp_f32_e32 v137, v117
	v_log_f32_e32 v134, v122
	v_log_f32_e32 v135, v123
	v_log_f32_e32 v120, v120
	v_log_f32_e32 v121, v121
	v_add_f32_e32 v116, 1.0, v138
	v_add_f32_e32 v117, 1.0, v139
	v_add_f32_e32 v118, 1.0, v136
	v_add_f32_e32 v119, 1.0, v137
	v_rcp_f32_e32 v146, v116
	v_mul_f32_e32 v122, s68, v120
	v_mul_f32_e32 v123, s68, v121
	v_mul_f32_e32 v120, s68, v134
	v_mul_f32_e32 v121, s68, v135
	v_rcp_f32_e32 v134, v118
	v_rcp_f32_e32 v147, v117
	v_rcp_f32_e32 v135, v119
	v_mul_f32_e32 v116, v124, v128
	v_mul_f32_e32 v117, v125, v129
	v_mul_f32_e32 v118, v126, v130
	v_mul_f32_e32 v119, v127, v131
	v_fma_f32 v124, v140, v146, v22
	v_fma_f32 v125, v141, v147, v23
	v_fma_f32 v126, v2, v134, v20
	v_fma_f32 v127, v3, v135, v21
	v_log_f32_e32 v124, v124
	v_log_f32_e32 v126, v126
	v_log_f32_e32 v125, v125
	v_log_f32_e32 v127, v127
	v_mul_f32_e32 v128, v144, v118
	v_mul_f32_e32 v129, v145, v119
	v_mul_f32_e32 v130, v142, v116
	v_mul_f32_e32 v131, v143, v117
	v_mul_f32_e32 v118, s68, v124
	v_mul_f32_e32 v119, s68, v125
	v_mul_f32_e32 v116, s68, v126
	v_mul_f32_e32 v117, s68, v127
	v_mul_f32_e32 v124, v136, v134
	v_mul_f32_e32 v125, v137, v135
	v_mul_f32_e32 v126, v138, v146
	v_mul_f32_e32 v127, v139, v147
	s_nop 0
	v_mul_f32_e32 v134, v140, v126
	v_mul_f32_e32 v135, v141, v127
	v_mul_f32_e32 v126, v2, v124
	v_mul_f32_e32 v127, v3, v125
	v_cvt_pk_bf16_f32 v124, v130, v131
	v_cvt_pk_bf16_f32 v125, v128, v129
	v_lshl_add_u64 v[128:129], s[30:31], 0, v[0:1]
	v_add_co_u32_e32 v128, vcc, 0x4400000, v128
	v_cvt_pk_bf16_f32 v126, v126, v127
	v_cvt_pk_bf16_f32 v127, v134, v135
	s_nop 1
	v_addc_co_u32_e32 v129, vcc, 0, v129, vcc
	global_store_dwordx4 v[128:129], v[124:127], off
.LBB0_343:
	v_cvt_pk_bf16_f32 v120, v120, v121
	v_cvt_pk_bf16_f32 v121, v122, v123
	v_cvt_pk_bf16_f32 v122, v116, v117
	v_lshl_add_u64 v[116:117], s[30:31], 0, v[0:1]
	s_and_b64 vcc, exec, s[8:9]
	v_cvt_pk_bf16_f32 v123, v118, v119
	global_store_dwordx4 v[116:117], v[120:123], off
	s_cbranch_vccnz .LBB0_347
	v_mul_f32_e32 v116, s96, v114
	v_mul_f32_e32 v117, s96, v115
	v_mul_f32_e32 v118, s96, v112
	v_mul_f32_e32 v119, s96, v113
	v_exp_f32_e32 v116, v116
	v_exp_f32_e32 v118, v118
	v_exp_f32_e32 v119, v119
	v_exp_f32_e32 v117, v117
	v_add_f32_e32 v118, 1.0, v118
	v_add_f32_e32 v119, 1.0, v119
	v_add_f32_e32 v116, 1.0, v116
	v_add_f32_e32 v117, 1.0, v117
	v_rcp_f32_e32 v118, v118
	v_rcp_f32_e32 v119, v119
	v_rcp_f32_e32 v116, v116
	v_rcp_f32_e32 v117, v117
	v_mul_f32_e32 v112, v112, v118
	v_mul_f32_e32 v113, v113, v119
	v_mul_f32_e32 v118, s96, v108
	v_mul_f32_e32 v119, s96, v109
	v_mul_f32_e32 v114, v114, v116
	v_mul_f32_e32 v115, v115, v117
	v_mul_f32_e32 v116, s96, v110
	v_mul_f32_e32 v117, s96, v111
	v_exp_f32_e32 v118, v118
	v_exp_f32_e32 v119, v119
	v_exp_f32_e32 v116, v116
	v_exp_f32_e32 v117, v117
	v_add_f32_e32 v118, 1.0, v118
	v_add_f32_e32 v119, 1.0, v119
	s_nop 0
	v_rcp_f32_e32 v118, v118
	v_add_f32_e32 v116, 1.0, v116
	v_add_f32_e32 v117, 1.0, v117
	v_rcp_f32_e32 v119, v119
	v_rcp_f32_e32 v116, v116
	v_rcp_f32_e32 v117, v117
	v_mul_f32_e32 v108, v108, v118
	v_mul_f32_e32 v109, v109, v119
	v_mul_f32_e32 v110, v110, v116
	v_mul_f32_e32 v111, v111, v117
	s_and_b64 vcc, exec, s[12:13]
	s_cbranch_vccz .LBB0_348

; __device__ __forceinline__ f32x4 silu4(f32x4 v) { return v * sigm4(v); }
; __device__ __forceinline__ u32x4 pack8(f32x4 v0, f32x4 v1) { u32x4 w; w.x = cvt_pk_bf16(v0[0], v0[1]); w.y = cvt_pk_bf16(v0[2], v0[3]); w.z = cvt_pk_bf16(v1[0], v1[1]); w.w = cvt_pk_bf16(v1[2], v1[3]); return w; }
; __device__ __forceinline__ void hg_gate4(f32x4& z, f32x4& key, const f32x4 l) {
;     const f32x4 zc = {__builtin_amdgcn_fmed3f(z[0], -80.f, 80.f), __builtin_amdgcn_fmed3f(z[1], -80.f, 80.f), __builtin_amdgcn_fmed3f(z[2], -80.f, 80.f), __builtin_amdgcn_fmed3f(z[3], -80.f, 80.f)};
;     const f32x4 t = zc * -1.4426950408889634f;
;     const f32x4 e = {__builtin_amdgcn_exp2f(t[0]), __builtin_amdgcn_exp2f(t[1]), __builtin_amdgcn_exp2f(t[2]), __builtin_amdgcn_exp2f(t[3])};
;     const f32x4 den = e + 1.0f;
;     const f32x4 sg = {__builtin_amdgcn_rcpf(den[0]), __builtin_amdgcn_rcpf(den[1]), __builtin_amdgcn_rcpf(den[2]), __builtin_amdgcn_rcpf(den[3])};
;     const f32x4 oml = 1.0f - l;
;     const f32x4 f = l + oml * sg;
;     z = (f32x4){__builtin_amdgcn_logf(f[0]), __builtin_amdgcn_logf(f[1]), __builtin_amdgcn_logf(f[2]), __builtin_amdgcn_logf(f[3])} * 0.6931471805599453f;
;     key = oml * (e * sg);
; }
;     __device__ __forceinline__ void operator()(const f32x4 (&acc)[2][2][4][2], const Unit& u, int wr, int wc, int fr_in, int fq_in) const {
;     ...
;                 for (int bj = 0; bj < 2; ++bj) {
;                     f32x4 v0 = acc[ai][bj][m][0], v1 = acc[ai][bj][m][1];
;                     if (type == 0) { v0 = silu4(v0); v1 = silu4(v1); }
;                     if (type == 4) { v0 = sigm4(v0); v1 = sigm4(v1); }
;                     if (type == 1 || type == 2) {
;                         f32x4 k0, k1;
;                         hg_gate4(v0, k0, lbv[bj][0]); hg_gate4(v1, k1, lbv[bj][1]);
;                         st16(base + tstride, roff + bj * HALF, pack8(k0, k1));
;                     }
;                     st16(base, roff + bj * HALF, pack8(v0, v1));
.LBB0_348:
	v_mul_f32_e32 v114, s96, v114
	v_mul_f32_e32 v115, s96, v115
	v_mul_f32_e32 v112, s96, v112
	v_mul_f32_e32 v113, s96, v113
	v_mul_f32_e32 v110, s96, v110
	v_mul_f32_e32 v111, s96, v111
	v_mul_f32_e32 v108, s96, v108
	v_mul_f32_e32 v109, s96, v109
	v_exp_f32_e32 v112, v112
	v_exp_f32_e32 v113, v113
	v_exp_f32_e32 v114, v114
	v_exp_f32_e32 v115, v115
	v_exp_f32_e32 v108, v108
	v_exp_f32_e32 v109, v109
	v_exp_f32_e32 v110, v110
	v_exp_f32_e32 v111, v111
	v_add_f32_e32 v114, 1.0, v114
	v_add_f32_e32 v115, 1.0, v115
	v_add_f32_e32 v112, 1.0, v112
	v_add_f32_e32 v113, 1.0, v113
	v_add_f32_e32 v108, 1.0, v108
	v_add_f32_e32 v109, 1.0, v109
	v_add_f32_e32 v110, 1.0, v110
	v_add_f32_e32 v111, 1.0, v111
	v_rcp_f32_e32 v112, v112
	v_rcp_f32_e32 v113, v113
	v_rcp_f32_e32 v114, v114
	v_rcp_f32_e32 v115, v115
	v_rcp_f32_e32 v108, v108
	v_rcp_f32_e32 v109, v109
	v_rcp_f32_e32 v110, v110
	v_rcp_f32_e32 v111, v111
	v_mov_b32_e32 v0, 0x20000
	s_and_b64 vcc, exec, s[10:11]
	v_lshl_add_u32 v0, v132, 1, v0
	s_cbranch_vccz .LBB0_346
.LBB0_349:
.LBB0_350:
	v_med3_f32 v112, v112, s95, v182
	v_med3_f32 v113, v113, s95, v182
	v_med3_f32 v114, v114, s95, v182
	v_med3_f32 v115, v115, s95, v182
	v_mul_f32_e32 v114, s96, v114
	v_mul_f32_e32 v115, s96, v115
	v_mul_f32_e32 v112, s96, v112
	v_mul_f32_e32 v113, s96, v113
	v_exp_f32_e32 v118, v114
	v_exp_f32_e32 v116, v112
	v_exp_f32_e32 v119, v115
	v_exp_f32_e32 v117, v113
	v_med3_f32 v108, v108, s95, v182
	v_med3_f32 v109, v109, s95, v182
	v_add_f32_e32 v112, 1.0, v118
	v_add_f32_e32 v113, 1.0, v119
	v_add_f32_e32 v114, 1.0, v116
	v_add_f32_e32 v115, 1.0, v117
	v_rcp_f32_e32 v122, v112
	v_rcp_f32_e32 v120, v114
	v_rcp_f32_e32 v123, v113
	v_rcp_f32_e32 v121, v115
	v_med3_f32 v110, v110, s95, v182
	v_med3_f32 v111, v111, s95, v182
	v_mul_f32_e32 v110, s96, v110
	v_mul_f32_e32 v111, s96, v111
	v_mul_f32_e32 v108, s96, v108
	v_mul_f32_e32 v109, s96, v109
	v_fma_f32 v112, v154, v122, v50
	v_fma_f32 v113, v155, v123, v51
	v_fma_f32 v114, v152, v120, v48
	v_fma_f32 v115, v153, v121, v49
	v_exp_f32_e32 v126, v108
	v_exp_f32_e32 v128, v110
	v_exp_f32_e32 v129, v111
	v_exp_f32_e32 v127, v109
	v_log_f32_e32 v124, v114
	v_log_f32_e32 v125, v115
	v_log_f32_e32 v112, v112
	v_log_f32_e32 v113, v113
	v_add_f32_e32 v108, 1.0, v128
	v_add_f32_e32 v109, 1.0, v129
	v_add_f32_e32 v110, 1.0, v126
	v_add_f32_e32 v111, 1.0, v127
	v_rcp_f32_e32 v130, v108
	v_mul_f32_e32 v114, s68, v112
	v_mul_f32_e32 v115, s68, v113
	v_mul_f32_e32 v112, s68, v124
	v_mul_f32_e32 v113, s68, v125
	v_rcp_f32_e32 v124, v110
	v_rcp_f32_e32 v131, v109
	v_rcp_f32_e32 v125, v111
	v_mul_f32_e32 v108, v116, v120
	v_mul_f32_e32 v109, v117, v121
	v_mul_f32_e32 v110, v118, v122
	v_mul_f32_e32 v111, v119, v123
	v_fma_f32 v116, v150, v130, v38
	v_fma_f32 v117, v151, v131, v39
	v_fma_f32 v118, v148, v124, v36
	v_fma_f32 v119, v149, v125, v37
	v_log_f32_e32 v116, v116
	v_log_f32_e32 v118, v118
	v_log_f32_e32 v117, v117
	v_log_f32_e32 v119, v119
	v_mul_f32_e32 v120, v154, v110
	v_mul_f32_e32 v121, v155, v111
	v_mul_f32_e32 v122, v152, v108
	v_mul_f32_e32 v123, v153, v109
	v_mul_f32_e32 v110, s68, v116
	v_mul_f32_e32 v111, s68, v117
	v_mul_f32_e32 v108, s68, v118
	v_mul_f32_e32 v109, s68, v119
	v_mul_f32_e32 v116, v126, v124
	v_mul_f32_e32 v117, v127, v125
	v_mul_f32_e32 v118, v128, v130
	v_mul_f32_e32 v119, v129, v131
	s_nop 0
	v_mul_f32_e32 v124, v150, v118
	v_mul_f32_e32 v125, v151, v119
	v_mul_f32_e32 v118, v148, v116
	v_mul_f32_e32 v119, v149, v117
	v_cvt_pk_bf16_f32 v116, v122, v123
	v_cvt_pk_bf16_f32 v117, v120, v121
	v_lshl_add_u64 v[120:121], s[30:31], 0, v[0:1]
	v_add_co_u32_e32 v120, vcc, 0x4400000, v120
	v_cvt_pk_bf16_f32 v118, v118, v119
	v_cvt_pk_bf16_f32 v119, v124, v125
	s_nop 1
	v_addc_co_u32_e32 v121, vcc, 0, v121, vcc
	global_store_dwordx4 v[120:121], v[116:119], off
.LBB0_351:
	v_cvt_pk_bf16_f32 v112, v112, v113
	v_cvt_pk_bf16_f32 v113, v114, v115
	v_cvt_pk_bf16_f32 v114, v108, v109
	v_lshl_add_u64 v[108:109], s[30:31], 0, v[0:1]
	s_and_b64 vcc, exec, s[8:9]
	v_cvt_pk_bf16_f32 v115, v110, v111
	global_store_dwordx4 v[108:109], v[112:115], off
	s_cbranch_vccnz .LBB0_355
	v_mul_f32_e32 v108, s96, v106
	v_mul_f32_e32 v109, s96, v107
	v_mul_f32_e32 v110, s96, v104
	v_mul_f32_e32 v111, s96, v105
	v_exp_f32_e32 v108, v108
	v_exp_f32_e32 v110, v110
	v_exp_f32_e32 v111, v111
	v_exp_f32_e32 v109, v109
	v_add_f32_e32 v110, 1.0, v110
	v_add_f32_e32 v111, 1.0, v111
	v_add_f32_e32 v108, 1.0, v108
	v_add_f32_e32 v109, 1.0, v109
	v_rcp_f32_e32 v110, v110
	v_rcp_f32_e32 v111, v111
	v_rcp_f32_e32 v108, v108
	v_rcp_f32_e32 v109, v109
	v_mul_f32_e32 v104, v104, v110
	v_mul_f32_e32 v105, v105, v111
	v_mul_f32_e32 v110, s96, v100
	v_mul_f32_e32 v111, s96, v101
	v_mul_f32_e32 v106, v106, v108
	v_mul_f32_e32 v107, v107, v109
	v_mul_f32_e32 v108, s96, v102
	v_mul_f32_e32 v109, s96, v103
	v_exp_f32_e32 v110, v110
	v_exp_f32_e32 v111, v111
	v_exp_f32_e32 v108, v108
	v_exp_f32_e32 v109, v109
	v_add_f32_e32 v110, 1.0, v110
	v_add_f32_e32 v111, 1.0, v111
	s_nop 0
	v_rcp_f32_e32 v110, v110
	v_add_f32_e32 v108, 1.0, v108
	v_add_f32_e32 v109, 1.0, v109
	v_rcp_f32_e32 v111, v111
	v_rcp_f32_e32 v108, v108
	v_rcp_f32_e32 v109, v109
	v_mul_f32_e32 v100, v100, v110
	v_mul_f32_e32 v101, v101, v111
	v_mul_f32_e32 v102, v102, v108
	v_mul_f32_e32 v103, v103, v109
	s_and_b64 vcc, exec, s[12:13]
	s_cbranch_vccz .LBB0_356

; __device__ __forceinline__ f32x4 sigm4(f32x4 v) { const f32x4 t = v * -1.4426950408889634f; f32x4 e = {__builtin_amdgcn_exp2f(t[0]), __builtin_amdgcn_exp2f(t[1]), __builtin_amdgcn_exp2f(t[2]), __builtin_amdgcn_exp2f(t[3])};
;     e = e + 1.0f; return (f32x4){__builtin_amdgcn_rcpf(e[0]), __builtin_amdgcn_rcpf(e[1]), __builtin_amdgcn_rcpf(e[2]), __builtin_amdgcn_rcpf(e[3])}; }
;     __device__ __forceinline__ void operator()(const f32x4 (&acc)[2][2][4][2], const Unit& u, int wr, int wc, int fr_in, int fq_in) const {
;     ...
;                     if (type == 4) { v0 = sigm4(v0); v1 = sigm4(v1); }
.LBB0_356:
	v_mul_f32_e32 v106, s96, v106
	v_mul_f32_e32 v107, s96, v107
	v_mul_f32_e32 v104, s96, v104
	v_mul_f32_e32 v105, s96, v105
	v_mul_f32_e32 v102, s96, v102
	v_mul_f32_e32 v103, s96, v103
	v_mul_f32_e32 v100, s96, v100
	v_mul_f32_e32 v101, s96, v101
	v_exp_f32_e32 v104, v104
	v_exp_f32_e32 v105, v105
	v_exp_f32_e32 v106, v106
	v_exp_f32_e32 v107, v107
	v_exp_f32_e32 v100, v100
	v_exp_f32_e32 v101, v101
	v_exp_f32_e32 v102, v102
	v_exp_f32_e32 v103, v103
	v_add_f32_e32 v106, 1.0, v106
	v_add_f32_e32 v107, 1.0, v107
	v_add_f32_e32 v104, 1.0, v104
	v_add_f32_e32 v105, 1.0, v105
	v_add_f32_e32 v100, 1.0, v100
	v_add_f32_e32 v101, 1.0, v101
	v_add_f32_e32 v102, 1.0, v102
	v_add_f32_e32 v103, 1.0, v103
	v_rcp_f32_e32 v104, v104
	v_rcp_f32_e32 v105, v105
	v_rcp_f32_e32 v106, v106
	v_rcp_f32_e32 v107, v107
	v_rcp_f32_e32 v100, v100
	v_rcp_f32_e32 v101, v101
	v_rcp_f32_e32 v102, v102
	v_rcp_f32_e32 v103, v103
	s_mov_b64 s[34:35], -1
	s_and_b64 vcc, exec, s[10:11]
	v_add_u32_e32 v0, 0x100, v0
	s_cbranch_vccz .LBB0_354

; __device__ __forceinline__ u32x4 pack8(f32x4 v0, f32x4 v1) { u32x4 w; w.x = cvt_pk_bf16(v0[0], v0[1]); w.y = cvt_pk_bf16(v0[2], v0[3]); w.z = cvt_pk_bf16(v1[0], v1[1]); w.w = cvt_pk_bf16(v1[2], v1[3]); return w; }
; __device__ __forceinline__ void hg_gate4(f32x4& z, f32x4& key, const f32x4 l) {
;     const f32x4 zc = {__builtin_amdgcn_fmed3f(z[0], -80.f, 80.f), __builtin_amdgcn_fmed3f(z[1], -80.f, 80.f), __builtin_amdgcn_fmed3f(z[2], -80.f, 80.f), __builtin_amdgcn_fmed3f(z[3], -80.f, 80.f)};
;     const f32x4 t = zc * -1.4426950408889634f;
;     const f32x4 e = {__builtin_amdgcn_exp2f(t[0]), __builtin_amdgcn_exp2f(t[1]), __builtin_amdgcn_exp2f(t[2]), __builtin_amdgcn_exp2f(t[3])};
;     const f32x4 den = e + 1.0f;
;     const f32x4 sg = {__builtin_amdgcn_rcpf(den[0]), __builtin_amdgcn_rcpf(den[1]), __builtin_amdgcn_rcpf(den[2]), __builtin_amdgcn_rcpf(den[3])};
;     const f32x4 oml = 1.0f - l;
;     const f32x4 f = l + oml * sg;
;     z = (f32x4){__builtin_amdgcn_logf(f[0]), __builtin_amdgcn_logf(f[1]), __builtin_amdgcn_logf(f[2]), __builtin_amdgcn_logf(f[3])} * 0.6931471805599453f;
;     key = oml * (e * sg);
; }
;     __device__ __forceinline__ void operator()(const f32x4 (&acc)[2][2][4][2], const Unit& u, int wr, int wc, int fr_in, int fq_in) const {
;     ...
;                     if (type == 1 || type == 2) {
;                         f32x4 k0, k1;
;                         hg_gate4(v0, k0, lbv[bj][0]); hg_gate4(v1, k1, lbv[bj][1]);
;                         st16(base + tstride, roff + bj * HALF, pack8(k0, k1));
;                     }
;                     st16(base, roff + bj * HALF, pack8(v0, v1));
.LBB0_358:
	v_med3_f32 v104, v104, s95, v182
	v_med3_f32 v105, v105, s95, v182
	v_med3_f32 v106, v106, s95, v182
	v_med3_f32 v107, v107, s95, v182
	v_mul_f32_e32 v106, s96, v106
	v_mul_f32_e32 v107, s96, v107
	v_mul_f32_e32 v104, s96, v104
	v_mul_f32_e32 v105, s96, v105
	v_exp_f32_e32 v110, v106
	v_exp_f32_e32 v108, v104
	v_exp_f32_e32 v111, v107
	v_exp_f32_e32 v109, v105
	v_med3_f32 v100, v100, s95, v182
	v_med3_f32 v101, v101, s95, v182
	v_add_f32_e32 v104, 1.0, v110
	v_add_f32_e32 v105, 1.0, v111
	v_add_f32_e32 v106, 1.0, v108
	v_add_f32_e32 v107, 1.0, v109
	v_rcp_f32_e32 v114, v104
	v_rcp_f32_e32 v112, v106
	v_rcp_f32_e32 v115, v105
	v_rcp_f32_e32 v113, v107
	v_med3_f32 v102, v102, s95, v182
	v_med3_f32 v103, v103, s95, v182
	v_mul_f32_e32 v102, s96, v102
	v_mul_f32_e32 v103, s96, v103
	v_mul_f32_e32 v100, s96, v100
	v_mul_f32_e32 v101, s96, v101
	v_fma_f32 v104, v144, v114, v26
	v_fma_f32 v105, v145, v115, v27
	v_fma_f32 v106, v142, v112, v24
	v_fma_f32 v107, v143, v113, v25
	v_exp_f32_e32 v118, v100
	v_exp_f32_e32 v120, v102
	v_exp_f32_e32 v121, v103
	v_exp_f32_e32 v119, v101
	v_log_f32_e32 v116, v106
	v_log_f32_e32 v117, v107
	v_log_f32_e32 v104, v104
	v_log_f32_e32 v105, v105
	v_add_f32_e32 v100, 1.0, v120
	v_add_f32_e32 v101, 1.0, v121
	v_add_f32_e32 v102, 1.0, v118
	v_add_f32_e32 v103, 1.0, v119
	v_rcp_f32_e32 v122, v100
	v_mul_f32_e32 v106, s68, v104
	v_mul_f32_e32 v107, s68, v105
	v_mul_f32_e32 v104, s68, v116
	v_mul_f32_e32 v105, s68, v117
	v_rcp_f32_e32 v116, v102
	v_rcp_f32_e32 v123, v101
	v_rcp_f32_e32 v117, v103
	v_mul_f32_e32 v100, v108, v112
	v_mul_f32_e32 v101, v109, v113
	v_mul_f32_e32 v102, v110, v114
	v_mul_f32_e32 v103, v111, v115
	v_fma_f32 v108, v140, v122, v22
	v_fma_f32 v109, v141, v123, v23
	v_fma_f32 v110, v2, v116, v20
	v_fma_f32 v111, v3, v117, v21
	v_log_f32_e32 v108, v108
	v_log_f32_e32 v110, v110
	v_log_f32_e32 v109, v109
	v_log_f32_e32 v111, v111
	v_mul_f32_e32 v112, v144, v102
	v_mul_f32_e32 v113, v145, v103
	v_mul_f32_e32 v114, v142, v100
	v_mul_f32_e32 v115, v143, v101
	v_mul_f32_e32 v102, s68, v108
	v_mul_f32_e32 v103, s68, v109
	v_mul_f32_e32 v100, s68, v110
	v_mul_f32_e32 v101, s68, v111
	v_mul_f32_e32 v108, v118, v116
	v_mul_f32_e32 v109, v119, v117
	v_mul_f32_e32 v110, v120, v122
	v_mul_f32_e32 v111, v121, v123
	s_nop 0
	v_mul_f32_e32 v116, v140, v110
	v_mul_f32_e32 v117, v141, v111
	v_mul_f32_e32 v110, v2, v108
	v_mul_f32_e32 v111, v3, v109
	v_cvt_pk_bf16_f32 v108, v114, v115
	v_cvt_pk_bf16_f32 v109, v112, v113
	v_lshl_add_u64 v[112:113], s[30:31], 0, v[0:1]
	v_add_co_u32_e32 v112, vcc, 0x4400000, v112
	v_cvt_pk_bf16_f32 v110, v110, v111
	v_cvt_pk_bf16_f32 v111, v116, v117
	s_nop 1
	v_addc_co_u32_e32 v113, vcc, 0, v113, vcc
	global_store_dwordx4 v[112:113], v[108:111], off
.LBB0_359:
	v_cvt_pk_bf16_f32 v104, v104, v105
	v_cvt_pk_bf16_f32 v105, v106, v107
	v_cvt_pk_bf16_f32 v106, v100, v101
	v_lshl_add_u64 v[100:101], s[30:31], 0, v[0:1]
	s_and_b64 vcc, exec, s[8:9]
	v_cvt_pk_bf16_f32 v107, v102, v103
	global_store_dwordx4 v[100:101], v[104:107], off
	s_cbranch_vccnz .LBB0_363
	v_mul_f32_e32 v100, s96, v98
	v_mul_f32_e32 v101, s96, v99
	v_mul_f32_e32 v102, s96, v96
	v_mul_f32_e32 v103, s96, v97
	v_exp_f32_e32 v100, v100
	v_exp_f32_e32 v102, v102
	v_exp_f32_e32 v103, v103
	v_exp_f32_e32 v101, v101
	v_add_f32_e32 v102, 1.0, v102
	v_add_f32_e32 v103, 1.0, v103
	v_add_f32_e32 v100, 1.0, v100
	v_add_f32_e32 v101, 1.0, v101
	v_rcp_f32_e32 v102, v102
	v_rcp_f32_e32 v103, v103
	v_rcp_f32_e32 v100, v100
	v_rcp_f32_e32 v101, v101
	v_mul_f32_e32 v96, v96, v102
	v_mul_f32_e32 v97, v97, v103
	v_mul_f32_e32 v102, s96, v92
	v_mul_f32_e32 v103, s96, v93
	v_mul_f32_e32 v98, v98, v100
	v_mul_f32_e32 v99, v99, v101
	v_mul_f32_e32 v100, s96, v94
	v_mul_f32_e32 v101, s96, v95
	v_exp_f32_e32 v102, v102
	v_exp_f32_e32 v103, v103
	v_exp_f32_e32 v100, v100
	v_exp_f32_e32 v101, v101
	v_add_f32_e32 v102, 1.0, v102
	v_add_f32_e32 v103, 1.0, v103
	s_nop 0
	v_rcp_f32_e32 v102, v102
	v_add_f32_e32 v100, 1.0, v100
	v_add_f32_e32 v101, 1.0, v101
	v_rcp_f32_e32 v103, v103
	v_rcp_f32_e32 v100, v100
	v_rcp_f32_e32 v101, v101
	v_mul_f32_e32 v92, v92, v102
	v_mul_f32_e32 v93, v93, v103
	v_mul_f32_e32 v94, v94, v100
	v_mul_f32_e32 v95, v95, v101
	s_and_b64 vcc, exec, s[12:13]
	s_cbranch_vccz .LBB0_364

; __device__ __forceinline__ f32x4 silu4(f32x4 v) { return v * sigm4(v); }
; __device__ __forceinline__ u32x4 pack8(f32x4 v0, f32x4 v1) { u32x4 w; w.x = cvt_pk_bf16(v0[0], v0[1]); w.y = cvt_pk_bf16(v0[2], v0[3]); w.z = cvt_pk_bf16(v1[0], v1[1]); w.w = cvt_pk_bf16(v1[2], v1[3]); return w; }
; __device__ __forceinline__ void hg_gate4(f32x4& z, f32x4& key, const f32x4 l) {
;     const f32x4 zc = {__builtin_amdgcn_fmed3f(z[0], -80.f, 80.f), __builtin_amdgcn_fmed3f(z[1], -80.f, 80.f), __builtin_amdgcn_fmed3f(z[2], -80.f, 80.f), __builtin_amdgcn_fmed3f(z[3], -80.f, 80.f)};
;     const f32x4 t = zc * -1.4426950408889634f;
;     const f32x4 e = {__builtin_amdgcn_exp2f(t[0]), __builtin_amdgcn_exp2f(t[1]), __builtin_amdgcn_exp2f(t[2]), __builtin_amdgcn_exp2f(t[3])};
;     const f32x4 den = e + 1.0f;
;     const f32x4 sg = {__builtin_amdgcn_rcpf(den[0]), __builtin_amdgcn_rcpf(den[1]), __builtin_amdgcn_rcpf(den[2]), __builtin_amdgcn_rcpf(den[3])};
;     const f32x4 oml = 1.0f - l;
;     const f32x4 f = l + oml * sg;
;     z = (f32x4){__builtin_amdgcn_logf(f[0]), __builtin_amdgcn_logf(f[1]), __builtin_amdgcn_logf(f[2]), __builtin_amdgcn_logf(f[3])} * 0.6931471805599453f;
;     key = oml * (e * sg);
; }
;     __device__ __forceinline__ void operator()(const f32x4 (&acc)[2][2][4][2], const Unit& u, int wr, int wc, int fr_in, int fq_in) const {
;     ...
;                 for (int bj = 0; bj < 2; ++bj) {
;                     f32x4 v0 = acc[ai][bj][m][0], v1 = acc[ai][bj][m][1];
;                     if (type == 0) { v0 = silu4(v0); v1 = silu4(v1); }
;                     if (type == 4) { v0 = sigm4(v0); v1 = sigm4(v1); }
;                     if (type == 1 || type == 2) {
;                         f32x4 k0, k1;
;                         hg_gate4(v0, k0, lbv[bj][0]); hg_gate4(v1, k1, lbv[bj][1]);
;                         st16(base + tstride, roff + bj * HALF, pack8(k0, k1));
;                     }
;                     st16(base, roff + bj * HALF, pack8(v0, v1));
.LBB0_364:
	v_mul_f32_e32 v98, s96, v98
	v_mul_f32_e32 v99, s96, v99
	v_mul_f32_e32 v96, s96, v96
	v_mul_f32_e32 v97, s96, v97
	v_mul_f32_e32 v94, s96, v94
	v_mul_f32_e32 v95, s96, v95
	v_mul_f32_e32 v92, s96, v92
	v_mul_f32_e32 v93, s96, v93
	v_exp_f32_e32 v96, v96
	v_exp_f32_e32 v97, v97
	v_exp_f32_e32 v98, v98
	v_exp_f32_e32 v99, v99
	v_exp_f32_e32 v92, v92
	v_exp_f32_e32 v93, v93
	v_exp_f32_e32 v94, v94
	v_exp_f32_e32 v95, v95
	v_add_f32_e32 v98, 1.0, v98
	v_add_f32_e32 v99, 1.0, v99
	v_add_f32_e32 v96, 1.0, v96
	v_add_f32_e32 v97, 1.0, v97
	v_add_f32_e32 v92, 1.0, v92
	v_add_f32_e32 v93, 1.0, v93
	v_add_f32_e32 v94, 1.0, v94
	v_add_f32_e32 v95, 1.0, v95
	v_rcp_f32_e32 v96, v96
	v_rcp_f32_e32 v97, v97
	v_rcp_f32_e32 v98, v98
	v_rcp_f32_e32 v99, v99
	v_rcp_f32_e32 v92, v92
	v_rcp_f32_e32 v93, v93
	v_rcp_f32_e32 v94, v94
	v_rcp_f32_e32 v95, v95
	v_mov_b32_e32 v0, 0x30000
	s_and_b64 vcc, exec, s[10:11]
	v_lshl_add_u32 v0, v132, 1, v0
	s_cbranch_vccz .LBB0_362
.LBB0_365:
.LBB0_366:
	v_med3_f32 v96, v96, s95, v182
	v_med3_f32 v97, v97, s95, v182
	v_med3_f32 v98, v98, s95, v182
	v_med3_f32 v99, v99, s95, v182
	v_mul_f32_e32 v98, s96, v98
	v_mul_f32_e32 v99, s96, v99
	v_mul_f32_e32 v96, s96, v96
	v_mul_f32_e32 v97, s96, v97
	v_exp_f32_e32 v102, v98
	v_exp_f32_e32 v100, v96
	v_exp_f32_e32 v103, v99
	v_exp_f32_e32 v101, v97
	v_med3_f32 v92, v92, s95, v182
	v_med3_f32 v93, v93, s95, v182
	v_add_f32_e32 v96, 1.0, v102
	v_add_f32_e32 v97, 1.0, v103
	v_add_f32_e32 v98, 1.0, v100
	v_add_f32_e32 v99, 1.0, v101
	v_rcp_f32_e32 v106, v96
	v_rcp_f32_e32 v104, v98
	v_rcp_f32_e32 v107, v97
	v_rcp_f32_e32 v105, v99
	v_med3_f32 v94, v94, s95, v182
	v_med3_f32 v95, v95, s95, v182
	v_mul_f32_e32 v94, s96, v94
	v_mul_f32_e32 v95, s96, v95
	v_mul_f32_e32 v92, s96, v92
	v_mul_f32_e32 v93, s96, v93
	v_fma_f32 v96, v154, v106, v50
	v_fma_f32 v97, v155, v107, v51
	v_fma_f32 v98, v152, v104, v48
	v_fma_f32 v99, v153, v105, v49
	v_exp_f32_e32 v110, v92
	v_exp_f32_e32 v112, v94
	v_exp_f32_e32 v113, v95
	v_exp_f32_e32 v111, v93
	v_log_f32_e32 v108, v98
	v_log_f32_e32 v109, v99
	v_log_f32_e32 v96, v96
	v_log_f32_e32 v97, v97
	v_add_f32_e32 v92, 1.0, v112
	v_add_f32_e32 v93, 1.0, v113
	v_add_f32_e32 v94, 1.0, v110
	v_add_f32_e32 v95, 1.0, v111
	v_rcp_f32_e32 v114, v92
	v_mul_f32_e32 v98, s68, v96
	v_mul_f32_e32 v99, s68, v97
	v_mul_f32_e32 v96, s68, v108
	v_mul_f32_e32 v97, s68, v109
	v_rcp_f32_e32 v108, v94
	v_rcp_f32_e32 v115, v93
	v_rcp_f32_e32 v109, v95
	v_mul_f32_e32 v92, v100, v104
	v_mul_f32_e32 v93, v101, v105
	v_mul_f32_e32 v94, v102, v106
	v_mul_f32_e32 v95, v103, v107
	v_fma_f32 v100, v150, v114, v38
	v_fma_f32 v101, v151, v115, v39
	v_fma_f32 v102, v148, v108, v36
	v_fma_f32 v103, v149, v109, v37
	v_log_f32_e32 v100, v100
	v_log_f32_e32 v102, v102
	v_log_f32_e32 v101, v101
	v_log_f32_e32 v103, v103
	v_mul_f32_e32 v104, v154, v94
	v_mul_f32_e32 v105, v155, v95
	v_mul_f32_e32 v106, v152, v92
	v_mul_f32_e32 v107, v153, v93
	v_mul_f32_e32 v94, s68, v100
	v_mul_f32_e32 v95, s68, v101
	v_mul_f32_e32 v92, s68, v102
	v_mul_f32_e32 v93, s68, v103
	v_mul_f32_e32 v100, v110, v108
	v_mul_f32_e32 v101, v111, v109
	v_mul_f32_e32 v102, v112, v114
	v_mul_f32_e32 v103, v113, v115
	s_nop 0
	v_mul_f32_e32 v108, v150, v102
	v_mul_f32_e32 v109, v151, v103
	v_mul_f32_e32 v102, v148, v100
	v_mul_f32_e32 v103, v149, v101
	v_cvt_pk_bf16_f32 v100, v106, v107
	v_cvt_pk_bf16_f32 v101, v104, v105
	v_lshl_add_u64 v[104:105], s[30:31], 0, v[0:1]
	v_add_co_u32_e32 v104, vcc, 0x4400000, v104
	v_cvt_pk_bf16_f32 v102, v102, v103
	v_cvt_pk_bf16_f32 v103, v108, v109
	s_nop 1
	v_addc_co_u32_e32 v105, vcc, 0, v105, vcc
	global_store_dwordx4 v[104:105], v[100:103], off
.LBB0_367:
	v_cvt_pk_bf16_f32 v96, v96, v97
	v_cvt_pk_bf16_f32 v97, v98, v99
	v_cvt_pk_bf16_f32 v98, v92, v93
	v_lshl_add_u64 v[92:93], s[30:31], 0, v[0:1]
	s_and_b64 vcc, exec, s[8:9]
	v_cvt_pk_bf16_f32 v99, v94, v95
	global_store_dwordx4 v[92:93], v[96:99], off
	s_cbranch_vccnz .LBB0_371
	v_mul_f32_e32 v92, s96, v90
	v_mul_f32_e32 v93, s96, v91
	v_mul_f32_e32 v94, s96, v88
	v_mul_f32_e32 v95, s96, v89
	v_exp_f32_e32 v92, v92
	v_exp_f32_e32 v94, v94
	v_exp_f32_e32 v95, v95
	v_exp_f32_e32 v93, v93
	v_add_f32_e32 v94, 1.0, v94
	v_add_f32_e32 v95, 1.0, v95
	v_add_f32_e32 v92, 1.0, v92
	v_add_f32_e32 v93, 1.0, v93
	v_rcp_f32_e32 v94, v94
	v_rcp_f32_e32 v95, v95
	v_rcp_f32_e32 v92, v92
	v_rcp_f32_e32 v93, v93
	v_mul_f32_e32 v88, v88, v94
	v_mul_f32_e32 v89, v89, v95
	v_mul_f32_e32 v94, s96, v84
	v_mul_f32_e32 v95, s96, v85
	v_mul_f32_e32 v90, v90, v92
	v_mul_f32_e32 v91, v91, v93
	v_mul_f32_e32 v92, s96, v86
	v_mul_f32_e32 v93, s96, v87
	v_exp_f32_e32 v94, v94
	v_exp_f32_e32 v95, v95
	v_exp_f32_e32 v92, v92
	v_exp_f32_e32 v93, v93
	v_add_f32_e32 v94, 1.0, v94
	v_add_f32_e32 v95, 1.0, v95
	s_nop 0
	v_rcp_f32_e32 v94, v94
	v_add_f32_e32 v92, 1.0, v92
	v_add_f32_e32 v93, 1.0, v93
	v_rcp_f32_e32 v95, v95
	v_rcp_f32_e32 v92, v92
	v_rcp_f32_e32 v93, v93
	v_mul_f32_e32 v84, v84, v94
	v_mul_f32_e32 v85, v85, v95
	v_mul_f32_e32 v86, v86, v92
	v_mul_f32_e32 v87, v87, v93
	s_and_b64 vcc, exec, s[12:13]
	s_cbranch_vccz .LBB0_372

; __device__ __forceinline__ f32x4 sigm4(f32x4 v) { const f32x4 t = v * -1.4426950408889634f; f32x4 e = {__builtin_amdgcn_exp2f(t[0]), __builtin_amdgcn_exp2f(t[1]), __builtin_amdgcn_exp2f(t[2]), __builtin_amdgcn_exp2f(t[3])};
;     e = e + 1.0f; return (f32x4){__builtin_amdgcn_rcpf(e[0]), __builtin_amdgcn_rcpf(e[1]), __builtin_amdgcn_rcpf(e[2]), __builtin_amdgcn_rcpf(e[3])}; }
;     __device__ __forceinline__ void operator()(const f32x4 (&acc)[2][2][4][2], const Unit& u, int wr, int wc, int fr_in, int fq_in) const {
;     ...
;                     if (type == 4) { v0 = sigm4(v0); v1 = sigm4(v1); }
.LBB0_372:
	v_mul_f32_e32 v90, s96, v90
	v_mul_f32_e32 v91, s96, v91
	v_mul_f32_e32 v88, s96, v88
	v_mul_f32_e32 v89, s96, v89
	v_mul_f32_e32 v86, s96, v86
	v_mul_f32_e32 v87, s96, v87
	v_mul_f32_e32 v84, s96, v84
	v_mul_f32_e32 v85, s96, v85
	v_exp_f32_e32 v88, v88
	v_exp_f32_e32 v89, v89
	v_exp_f32_e32 v90, v90
	v_exp_f32_e32 v91, v91
	v_exp_f32_e32 v84, v84
	v_exp_f32_e32 v85, v85
	v_exp_f32_e32 v86, v86
	v_exp_f32_e32 v87, v87
	v_add_f32_e32 v90, 1.0, v90
	v_add_f32_e32 v91, 1.0, v91
	v_add_f32_e32 v88, 1.0, v88
	v_add_f32_e32 v89, 1.0, v89
	v_add_f32_e32 v84, 1.0, v84
	v_add_f32_e32 v85, 1.0, v85
	v_add_f32_e32 v86, 1.0, v86
	v_add_f32_e32 v87, 1.0, v87
	v_rcp_f32_e32 v88, v88
	v_rcp_f32_e32 v89, v89
	v_rcp_f32_e32 v90, v90
	v_rcp_f32_e32 v91, v91
	v_rcp_f32_e32 v84, v84
	v_rcp_f32_e32 v85, v85
	v_rcp_f32_e32 v86, v86
	v_rcp_f32_e32 v87, v87
	s_mov_b64 s[34:35], -1
	s_and_b64 vcc, exec, s[10:11]
	v_add_u32_e32 v0, 0x100, v0
	s_cbranch_vccz .LBB0_370

; __device__ __forceinline__ u32x4 pack8(f32x4 v0, f32x4 v1) { u32x4 w; w.x = cvt_pk_bf16(v0[0], v0[1]); w.y = cvt_pk_bf16(v0[2], v0[3]); w.z = cvt_pk_bf16(v1[0], v1[1]); w.w = cvt_pk_bf16(v1[2], v1[3]); return w; }
; __device__ __forceinline__ void hg_gate4(f32x4& z, f32x4& key, const f32x4 l) {
;     const f32x4 zc = {__builtin_amdgcn_fmed3f(z[0], -80.f, 80.f), __builtin_amdgcn_fmed3f(z[1], -80.f, 80.f), __builtin_amdgcn_fmed3f(z[2], -80.f, 80.f), __builtin_amdgcn_fmed3f(z[3], -80.f, 80.f)};
;     const f32x4 t = zc * -1.4426950408889634f;
;     const f32x4 e = {__builtin_amdgcn_exp2f(t[0]), __builtin_amdgcn_exp2f(t[1]), __builtin_amdgcn_exp2f(t[2]), __builtin_amdgcn_exp2f(t[3])};
;     const f32x4 den = e + 1.0f;
;     const f32x4 sg = {__builtin_amdgcn_rcpf(den[0]), __builtin_amdgcn_rcpf(den[1]), __builtin_amdgcn_rcpf(den[2]), __builtin_amdgcn_rcpf(den[3])};
;     const f32x4 oml = 1.0f - l;
;     const f32x4 f = l + oml * sg;
;     z = (f32x4){__builtin_amdgcn_logf(f[0]), __builtin_amdgcn_logf(f[1]), __builtin_amdgcn_logf(f[2]), __builtin_amdgcn_logf(f[3])} * 0.6931471805599453f;
;     key = oml * (e * sg);
; }
;     __device__ __forceinline__ void operator()(const f32x4 (&acc)[2][2][4][2], const Unit& u, int wr, int wc, int fr_in, int fq_in) const {
;     ...
;                     if (type == 1 || type == 2) {
;                         f32x4 k0, k1;
;                         hg_gate4(v0, k0, lbv[bj][0]); hg_gate4(v1, k1, lbv[bj][1]);
;                         st16(base + tstride, roff + bj * HALF, pack8(k0, k1));
;                     }
;                     st16(base, roff + bj * HALF, pack8(v0, v1));
.LBB0_374:
	v_med3_f32 v88, v88, s95, v182
	v_med3_f32 v89, v89, s95, v182
	v_med3_f32 v90, v90, s95, v182
	v_med3_f32 v91, v91, s95, v182
	v_mul_f32_e32 v90, s96, v90
	v_mul_f32_e32 v91, s96, v91
	v_mul_f32_e32 v88, s96, v88
	v_mul_f32_e32 v89, s96, v89
	v_exp_f32_e32 v94, v90
	v_exp_f32_e32 v92, v88
	v_exp_f32_e32 v95, v91
	v_exp_f32_e32 v93, v89
	v_med3_f32 v84, v84, s95, v182
	v_med3_f32 v85, v85, s95, v182
	v_add_f32_e32 v88, 1.0, v94
	v_add_f32_e32 v89, 1.0, v95
	v_add_f32_e32 v90, 1.0, v92
	v_add_f32_e32 v91, 1.0, v93
	v_rcp_f32_e32 v98, v88
	v_rcp_f32_e32 v96, v90
	v_rcp_f32_e32 v99, v89
	v_rcp_f32_e32 v97, v91
	v_med3_f32 v86, v86, s95, v182
	v_med3_f32 v87, v87, s95, v182
	v_mul_f32_e32 v86, s96, v86
	v_mul_f32_e32 v87, s96, v87
	v_mul_f32_e32 v84, s96, v84
	v_mul_f32_e32 v85, s96, v85
	v_fma_f32 v88, v144, v98, v26
	v_fma_f32 v89, v145, v99, v27
	v_fma_f32 v90, v142, v96, v24
	v_fma_f32 v91, v143, v97, v25
	v_exp_f32_e32 v102, v84
	v_exp_f32_e32 v104, v86
	v_exp_f32_e32 v105, v87
	v_exp_f32_e32 v103, v85
	v_log_f32_e32 v100, v90
	v_log_f32_e32 v101, v91
	v_log_f32_e32 v88, v88
	v_log_f32_e32 v89, v89
	v_add_f32_e32 v84, 1.0, v104
	v_add_f32_e32 v85, 1.0, v105
	v_add_f32_e32 v86, 1.0, v102
	v_add_f32_e32 v87, 1.0, v103
	v_rcp_f32_e32 v106, v84
	v_mul_f32_e32 v90, s68, v88
	v_mul_f32_e32 v91, s68, v89
	v_mul_f32_e32 v88, s68, v100
	v_mul_f32_e32 v89, s68, v101
	v_rcp_f32_e32 v100, v86
	v_rcp_f32_e32 v107, v85
	v_rcp_f32_e32 v101, v87
	v_mul_f32_e32 v84, v92, v96
	v_mul_f32_e32 v85, v93, v97
	v_mul_f32_e32 v86, v94, v98
	v_mul_f32_e32 v87, v95, v99
	v_fma_f32 v92, v140, v106, v22
	v_fma_f32 v93, v141, v107, v23
	v_fma_f32 v94, v2, v100, v20
	v_fma_f32 v95, v3, v101, v21
	v_log_f32_e32 v92, v92
	v_log_f32_e32 v94, v94
	v_log_f32_e32 v93, v93
	v_log_f32_e32 v95, v95
	v_mul_f32_e32 v96, v144, v86
	v_mul_f32_e32 v97, v145, v87
	v_mul_f32_e32 v98, v142, v84
	v_mul_f32_e32 v99, v143, v85
	v_mul_f32_e32 v86, s68, v92
	v_mul_f32_e32 v87, s68, v93
	v_mul_f32_e32 v84, s68, v94
	v_mul_f32_e32 v85, s68, v95
	v_mul_f32_e32 v92, v102, v100
	v_mul_f32_e32 v93, v103, v101
	v_mul_f32_e32 v94, v104, v106
	v_mul_f32_e32 v95, v105, v107
	s_nop 0
	v_mul_f32_e32 v100, v140, v94
	v_mul_f32_e32 v101, v141, v95
	v_mul_f32_e32 v94, v2, v92
	v_mul_f32_e32 v95, v3, v93
	v_cvt_pk_bf16_f32 v92, v98, v99
	v_cvt_pk_bf16_f32 v93, v96, v97
	v_lshl_add_u64 v[96:97], s[30:31], 0, v[0:1]
	v_add_co_u32_e32 v96, vcc, 0x4400000, v96
	v_cvt_pk_bf16_f32 v94, v94, v95
	v_cvt_pk_bf16_f32 v95, v100, v101
	s_nop 1
	v_addc_co_u32_e32 v97, vcc, 0, v97, vcc
	global_store_dwordx4 v[96:97], v[92:95], off
.LBB0_375:
	v_cvt_pk_bf16_f32 v88, v88, v89
	v_cvt_pk_bf16_f32 v89, v90, v91
	v_cvt_pk_bf16_f32 v90, v84, v85
	v_lshl_add_u64 v[84:85], s[30:31], 0, v[0:1]
	s_and_b64 vcc, exec, s[8:9]
	v_cvt_pk_bf16_f32 v91, v86, v87
	global_store_dwordx4 v[84:85], v[88:91], off
	s_cbranch_vccnz .LBB0_379
	v_mul_f32_e32 v84, s96, v82
	v_mul_f32_e32 v85, s96, v83
	v_mul_f32_e32 v86, s96, v80
	v_mul_f32_e32 v87, s96, v81
	v_exp_f32_e32 v84, v84
	v_exp_f32_e32 v86, v86
	v_exp_f32_e32 v87, v87
	v_exp_f32_e32 v85, v85
	v_add_f32_e32 v86, 1.0, v86
	v_add_f32_e32 v87, 1.0, v87
	v_add_f32_e32 v84, 1.0, v84
	v_add_f32_e32 v85, 1.0, v85
	v_rcp_f32_e32 v86, v86
	v_rcp_f32_e32 v87, v87
	v_rcp_f32_e32 v84, v84
	v_rcp_f32_e32 v85, v85
	v_mul_f32_e32 v80, v80, v86
	v_mul_f32_e32 v81, v81, v87
	v_mul_f32_e32 v86, s96, v76
	v_mul_f32_e32 v87, s96, v77
	v_mul_f32_e32 v82, v82, v84
	v_mul_f32_e32 v83, v83, v85
	v_mul_f32_e32 v84, s96, v78
	v_mul_f32_e32 v85, s96, v79
	v_exp_f32_e32 v86, v86
	v_exp_f32_e32 v87, v87
	v_exp_f32_e32 v84, v84
	v_exp_f32_e32 v85, v85
	v_add_f32_e32 v86, 1.0, v86
	v_add_f32_e32 v87, 1.0, v87
	s_nop 0
	v_rcp_f32_e32 v86, v86
	v_add_f32_e32 v84, 1.0, v84
	v_add_f32_e32 v85, 1.0, v85
	v_rcp_f32_e32 v87, v87
	v_rcp_f32_e32 v84, v84
	v_rcp_f32_e32 v85, v85
	v_mul_f32_e32 v76, v76, v86
	v_mul_f32_e32 v77, v77, v87
	v_mul_f32_e32 v78, v78, v84
	v_mul_f32_e32 v79, v79, v85
	s_and_b64 vcc, exec, s[12:13]
	s_cbranch_vccz .LBB0_380

; __device__ __forceinline__ f32x4 silu4(f32x4 v) { return v * sigm4(v); }
; __device__ __forceinline__ u32x4 pack8(f32x4 v0, f32x4 v1) { u32x4 w; w.x = cvt_pk_bf16(v0[0], v0[1]); w.y = cvt_pk_bf16(v0[2], v0[3]); w.z = cvt_pk_bf16(v1[0], v1[1]); w.w = cvt_pk_bf16(v1[2], v1[3]); return w; }
; __device__ __forceinline__ void hg_gate4(f32x4& z, f32x4& key, const f32x4 l) {
;     const f32x4 zc = {__builtin_amdgcn_fmed3f(z[0], -80.f, 80.f), __builtin_amdgcn_fmed3f(z[1], -80.f, 80.f), __builtin_amdgcn_fmed3f(z[2], -80.f, 80.f), __builtin_amdgcn_fmed3f(z[3], -80.f, 80.f)};
;     const f32x4 t = zc * -1.4426950408889634f;
;     const f32x4 e = {__builtin_amdgcn_exp2f(t[0]), __builtin_amdgcn_exp2f(t[1]), __builtin_amdgcn_exp2f(t[2]), __builtin_amdgcn_exp2f(t[3])};
;     const f32x4 den = e + 1.0f;
;     const f32x4 sg = {__builtin_amdgcn_rcpf(den[0]), __builtin_amdgcn_rcpf(den[1]), __builtin_amdgcn_rcpf(den[2]), __builtin_amdgcn_rcpf(den[3])};
;     const f32x4 oml = 1.0f - l;
;     const f32x4 f = l + oml * sg;
;     z = (f32x4){__builtin_amdgcn_logf(f[0]), __builtin_amdgcn_logf(f[1]), __builtin_amdgcn_logf(f[2]), __builtin_amdgcn_logf(f[3])} * 0.6931471805599453f;
;     key = oml * (e * sg);
; }
;     __device__ __forceinline__ void operator()(const f32x4 (&acc)[2][2][4][2], const Unit& u, int wr, int wc, int fr_in, int fq_in) const {
;     ...
;                 for (int bj = 0; bj < 2; ++bj) {
;                     f32x4 v0 = acc[ai][bj][m][0], v1 = acc[ai][bj][m][1];
;                     if (type == 0) { v0 = silu4(v0); v1 = silu4(v1); }
;                     if (type == 4) { v0 = sigm4(v0); v1 = sigm4(v1); }
;                     if (type == 1 || type == 2) {
;                         f32x4 k0, k1;
;                         hg_gate4(v0, k0, lbv[bj][0]); hg_gate4(v1, k1, lbv[bj][1]);
;                         st16(base + tstride, roff + bj * HALF, pack8(k0, k1));
;                     }
;                     st16(base, roff + bj * HALF, pack8(v0, v1));
.LBB0_380:
	v_mul_f32_e32 v82, s96, v82
	v_mul_f32_e32 v83, s96, v83
	v_mul_f32_e32 v80, s96, v80
	v_mul_f32_e32 v81, s96, v81
	v_mul_f32_e32 v78, s96, v78
	v_mul_f32_e32 v79, s96, v79
	v_mul_f32_e32 v76, s96, v76
	v_mul_f32_e32 v77, s96, v77
	v_exp_f32_e32 v80, v80
	v_exp_f32_e32 v81, v81
	v_exp_f32_e32 v82, v82
	v_exp_f32_e32 v83, v83
	v_exp_f32_e32 v76, v76
	v_exp_f32_e32 v77, v77
	v_exp_f32_e32 v78, v78
	v_exp_f32_e32 v79, v79
	v_add_f32_e32 v82, 1.0, v82
	v_add_f32_e32 v83, 1.0, v83
	v_add_f32_e32 v80, 1.0, v80
	v_add_f32_e32 v81, 1.0, v81
	v_add_f32_e32 v76, 1.0, v76
	v_add_f32_e32 v77, 1.0, v77
	v_add_f32_e32 v78, 1.0, v78
	v_add_f32_e32 v79, 1.0, v79
	v_rcp_f32_e32 v80, v80
	v_rcp_f32_e32 v81, v81
	v_rcp_f32_e32 v82, v82
	v_rcp_f32_e32 v83, v83
	v_rcp_f32_e32 v76, v76
	v_rcp_f32_e32 v77, v77
	v_rcp_f32_e32 v78, v78
	v_rcp_f32_e32 v79, v79
	v_mov_b32_e32 v0, 0x80000
	s_and_b64 vcc, exec, s[10:11]
	v_lshl_add_u32 v0, v132, 1, v0
	s_cbranch_vccz .LBB0_378
.LBB0_381:
.LBB0_382:
	v_med3_f32 v80, v80, s95, v182
	v_med3_f32 v81, v81, s95, v182
	v_med3_f32 v82, v82, s95, v182
	v_med3_f32 v83, v83, s95, v182
	v_mul_f32_e32 v82, s96, v82
	v_mul_f32_e32 v83, s96, v83
	v_mul_f32_e32 v80, s96, v80
	v_mul_f32_e32 v81, s96, v81
	v_exp_f32_e32 v86, v82
	v_exp_f32_e32 v84, v80
	v_exp_f32_e32 v87, v83
	v_exp_f32_e32 v85, v81
	v_med3_f32 v76, v76, s95, v182
	v_med3_f32 v77, v77, s95, v182
	v_add_f32_e32 v80, 1.0, v86
	v_add_f32_e32 v81, 1.0, v87
	v_add_f32_e32 v82, 1.0, v84
	v_add_f32_e32 v83, 1.0, v85
	v_rcp_f32_e32 v90, v80
	v_rcp_f32_e32 v88, v82
	v_rcp_f32_e32 v91, v81
	v_rcp_f32_e32 v89, v83
	v_med3_f32 v78, v78, s95, v182
	v_med3_f32 v79, v79, s95, v182
	v_mul_f32_e32 v78, s96, v78
	v_mul_f32_e32 v79, s96, v79
	v_mul_f32_e32 v76, s96, v76
	v_mul_f32_e32 v77, s96, v77
	v_fma_f32 v80, v154, v90, v50
	v_fma_f32 v81, v155, v91, v51
	v_fma_f32 v82, v152, v88, v48
	v_fma_f32 v83, v153, v89, v49
	v_exp_f32_e32 v94, v76
	v_exp_f32_e32 v96, v78
	v_exp_f32_e32 v97, v79
	v_exp_f32_e32 v95, v77
	v_log_f32_e32 v92, v82
	v_log_f32_e32 v93, v83
	v_log_f32_e32 v80, v80
	v_log_f32_e32 v81, v81
	v_add_f32_e32 v76, 1.0, v96
	v_add_f32_e32 v77, 1.0, v97
	v_add_f32_e32 v78, 1.0, v94
	v_add_f32_e32 v79, 1.0, v95
	v_rcp_f32_e32 v98, v76
	v_mul_f32_e32 v82, s68, v80
	v_mul_f32_e32 v83, s68, v81
	v_mul_f32_e32 v80, s68, v92
	v_mul_f32_e32 v81, s68, v93
	v_rcp_f32_e32 v92, v78
	v_rcp_f32_e32 v99, v77
	v_rcp_f32_e32 v93, v79
	v_mul_f32_e32 v76, v84, v88
	v_mul_f32_e32 v77, v85, v89
	v_mul_f32_e32 v78, v86, v90
	v_mul_f32_e32 v79, v87, v91
	v_fma_f32 v84, v150, v98, v38
	v_fma_f32 v85, v151, v99, v39
	v_fma_f32 v86, v148, v92, v36
	v_fma_f32 v87, v149, v93, v37
	v_log_f32_e32 v84, v84
	v_log_f32_e32 v86, v86
	v_log_f32_e32 v85, v85
	v_log_f32_e32 v87, v87
	v_mul_f32_e32 v88, v154, v78
	v_mul_f32_e32 v89, v155, v79
	v_mul_f32_e32 v90, v152, v76
	v_mul_f32_e32 v91, v153, v77
	v_mul_f32_e32 v78, s68, v84
	v_mul_f32_e32 v79, s68, v85
	v_mul_f32_e32 v76, s68, v86
	v_mul_f32_e32 v77, s68, v87
	v_mul_f32_e32 v84, v94, v92
	v_mul_f32_e32 v85, v95, v93
	v_mul_f32_e32 v86, v96, v98
	v_mul_f32_e32 v87, v97, v99
	s_nop 0
	v_mul_f32_e32 v92, v150, v86
	v_mul_f32_e32 v93, v151, v87
	v_mul_f32_e32 v86, v148, v84
	v_mul_f32_e32 v87, v149, v85
	v_cvt_pk_bf16_f32 v84, v90, v91
	v_cvt_pk_bf16_f32 v85, v88, v89
	v_lshl_add_u64 v[88:89], s[30:31], 0, v[0:1]
	v_add_co_u32_e32 v88, vcc, 0x4400000, v88
	v_cvt_pk_bf16_f32 v86, v86, v87
	v_cvt_pk_bf16_f32 v87, v92, v93
	s_nop 1
	v_addc_co_u32_e32 v89, vcc, 0, v89, vcc
	global_store_dwordx4 v[88:89], v[84:87], off
.LBB0_383:
	v_cvt_pk_bf16_f32 v80, v80, v81
	v_cvt_pk_bf16_f32 v81, v82, v83
	v_cvt_pk_bf16_f32 v82, v76, v77
	v_lshl_add_u64 v[76:77], s[30:31], 0, v[0:1]
	s_and_b64 vcc, exec, s[8:9]
	v_cvt_pk_bf16_f32 v83, v78, v79
	global_store_dwordx4 v[76:77], v[80:83], off
	s_cbranch_vccnz .LBB0_387
	v_mul_f32_e32 v76, s96, v74
	v_mul_f32_e32 v77, s96, v75
	v_mul_f32_e32 v78, s96, v72
	v_mul_f32_e32 v79, s96, v73
	v_exp_f32_e32 v76, v76
	v_exp_f32_e32 v78, v78
	v_exp_f32_e32 v79, v79
	v_exp_f32_e32 v77, v77
	v_add_f32_e32 v78, 1.0, v78
	v_add_f32_e32 v79, 1.0, v79
	v_add_f32_e32 v76, 1.0, v76
	v_add_f32_e32 v77, 1.0, v77
	v_rcp_f32_e32 v78, v78
	v_rcp_f32_e32 v79, v79
	v_rcp_f32_e32 v76, v76
	v_rcp_f32_e32 v77, v77
	v_mul_f32_e32 v72, v72, v78
	v_mul_f32_e32 v73, v73, v79
	v_mul_f32_e32 v78, s96, v68
	v_mul_f32_e32 v79, s96, v69
	v_mul_f32_e32 v74, v74, v76
	v_mul_f32_e32 v75, v75, v77
	v_mul_f32_e32 v76, s96, v70
	v_mul_f32_e32 v77, s96, v71
	v_exp_f32_e32 v78, v78
	v_exp_f32_e32 v79, v79
	v_exp_f32_e32 v76, v76
	v_exp_f32_e32 v77, v77
	v_add_f32_e32 v78, 1.0, v78
	v_add_f32_e32 v79, 1.0, v79
	s_nop 0
	v_rcp_f32_e32 v78, v78
	v_add_f32_e32 v76, 1.0, v76
	v_add_f32_e32 v77, 1.0, v77
	v_rcp_f32_e32 v79, v79
	v_rcp_f32_e32 v76, v76
	v_rcp_f32_e32 v77, v77
	v_mul_f32_e32 v68, v68, v78
	v_mul_f32_e32 v69, v69, v79
	v_mul_f32_e32 v70, v70, v76
	v_mul_f32_e32 v71, v71, v77
	s_and_b64 vcc, exec, s[12:13]
	s_cbranch_vccz .LBB0_388

; __device__ __forceinline__ f32x4 sigm4(f32x4 v) { const f32x4 t = v * -1.4426950408889634f; f32x4 e = {__builtin_amdgcn_exp2f(t[0]), __builtin_amdgcn_exp2f(t[1]), __builtin_amdgcn_exp2f(t[2]), __builtin_amdgcn_exp2f(t[3])};
;     e = e + 1.0f; return (f32x4){__builtin_amdgcn_rcpf(e[0]), __builtin_amdgcn_rcpf(e[1]), __builtin_amdgcn_rcpf(e[2]), __builtin_amdgcn_rcpf(e[3])}; }
;     __device__ __forceinline__ void operator()(const f32x4 (&acc)[2][2][4][2], const Unit& u, int wr, int wc, int fr_in, int fq_in) const {
;     ...
;                     if (type == 4) { v0 = sigm4(v0); v1 = sigm4(v1); }
.LBB0_388:
	v_mul_f32_e32 v74, s96, v74
	v_mul_f32_e32 v75, s96, v75
	v_mul_f32_e32 v72, s96, v72
	v_mul_f32_e32 v73, s96, v73
	v_mul_f32_e32 v70, s96, v70
	v_mul_f32_e32 v71, s96, v71
	v_mul_f32_e32 v68, s96, v68
	v_mul_f32_e32 v69, s96, v69
	v_exp_f32_e32 v72, v72
	v_exp_f32_e32 v73, v73
	v_exp_f32_e32 v74, v74
	v_exp_f32_e32 v75, v75
	v_exp_f32_e32 v68, v68
	v_exp_f32_e32 v69, v69
	v_exp_f32_e32 v70, v70
	v_exp_f32_e32 v71, v71
	v_add_f32_e32 v74, 1.0, v74
	v_add_f32_e32 v75, 1.0, v75
	v_add_f32_e32 v72, 1.0, v72
	v_add_f32_e32 v73, 1.0, v73
	v_add_f32_e32 v68, 1.0, v68
	v_add_f32_e32 v69, 1.0, v69
	v_add_f32_e32 v70, 1.0, v70
	v_add_f32_e32 v71, 1.0, v71
	v_rcp_f32_e32 v72, v72
	v_rcp_f32_e32 v73, v73
	v_rcp_f32_e32 v74, v74
	v_rcp_f32_e32 v75, v75
	v_rcp_f32_e32 v68, v68
	v_rcp_f32_e32 v69, v69
	v_rcp_f32_e32 v70, v70
	v_rcp_f32_e32 v71, v71
	s_mov_b64 s[34:35], -1
	s_and_b64 vcc, exec, s[10:11]
	v_add_u32_e32 v0, 0x100, v0
	s_cbranch_vccz .LBB0_386

; __device__ __forceinline__ u32x4 pack8(f32x4 v0, f32x4 v1) { u32x4 w; w.x = cvt_pk_bf16(v0[0], v0[1]); w.y = cvt_pk_bf16(v0[2], v0[3]); w.z = cvt_pk_bf16(v1[0], v1[1]); w.w = cvt_pk_bf16(v1[2], v1[3]); return w; }
; __device__ __forceinline__ void hg_gate4(f32x4& z, f32x4& key, const f32x4 l) {
;     const f32x4 zc = {__builtin_amdgcn_fmed3f(z[0], -80.f, 80.f), __builtin_amdgcn_fmed3f(z[1], -80.f, 80.f), __builtin_amdgcn_fmed3f(z[2], -80.f, 80.f), __builtin_amdgcn_fmed3f(z[3], -80.f, 80.f)};
;     const f32x4 t = zc * -1.4426950408889634f;
;     const f32x4 e = {__builtin_amdgcn_exp2f(t[0]), __builtin_amdgcn_exp2f(t[1]), __builtin_amdgcn_exp2f(t[2]), __builtin_amdgcn_exp2f(t[3])};
;     const f32x4 den = e + 1.0f;
;     const f32x4 sg = {__builtin_amdgcn_rcpf(den[0]), __builtin_amdgcn_rcpf(den[1]), __builtin_amdgcn_rcpf(den[2]), __builtin_amdgcn_rcpf(den[3])};
;     const f32x4 oml = 1.0f - l;
;     const f32x4 f = l + oml * sg;
;     z = (f32x4){__builtin_amdgcn_logf(f[0]), __builtin_amdgcn_logf(f[1]), __builtin_amdgcn_logf(f[2]), __builtin_amdgcn_logf(f[3])} * 0.6931471805599453f;
;     key = oml * (e * sg);
; }
;     __device__ __forceinline__ void operator()(const f32x4 (&acc)[2][2][4][2], const Unit& u, int wr, int wc, int fr_in, int fq_in) const {
;     ...
;                     if (type == 1 || type == 2) {
;                         f32x4 k0, k1;
;                         hg_gate4(v0, k0, lbv[bj][0]); hg_gate4(v1, k1, lbv[bj][1]);
;                         st16(base + tstride, roff + bj * HALF, pack8(k0, k1));
;                     }
;                     st16(base, roff + bj * HALF, pack8(v0, v1));
.LBB0_390:
	v_med3_f32 v72, v72, s95, v182
	v_med3_f32 v73, v73, s95, v182
	v_med3_f32 v74, v74, s95, v182
	v_med3_f32 v75, v75, s95, v182
	v_mul_f32_e32 v74, s96, v74
	v_mul_f32_e32 v75, s96, v75
	v_mul_f32_e32 v72, s96, v72
	v_mul_f32_e32 v73, s96, v73
	v_exp_f32_e32 v78, v74
	v_exp_f32_e32 v76, v72
	v_exp_f32_e32 v79, v75
	v_exp_f32_e32 v77, v73
	v_med3_f32 v68, v68, s95, v182
	v_med3_f32 v69, v69, s95, v182
	v_add_f32_e32 v72, 1.0, v78
	v_add_f32_e32 v73, 1.0, v79
	v_add_f32_e32 v74, 1.0, v76
	v_add_f32_e32 v75, 1.0, v77
	v_rcp_f32_e32 v82, v72
	v_rcp_f32_e32 v80, v74
	v_rcp_f32_e32 v83, v73
	v_rcp_f32_e32 v81, v75
	v_med3_f32 v70, v70, s95, v182
	v_med3_f32 v71, v71, s95, v182
	v_mul_f32_e32 v70, s96, v70
	v_mul_f32_e32 v71, s96, v71
	v_mul_f32_e32 v68, s96, v68
	v_mul_f32_e32 v69, s96, v69
	v_fma_f32 v72, v144, v82, v26
	v_fma_f32 v73, v145, v83, v27
	v_fma_f32 v74, v142, v80, v24
	v_fma_f32 v75, v143, v81, v25
	v_exp_f32_e32 v86, v68
	v_exp_f32_e32 v88, v70
	v_exp_f32_e32 v89, v71
	v_exp_f32_e32 v87, v69
	v_log_f32_e32 v84, v74
	v_log_f32_e32 v85, v75
	v_log_f32_e32 v72, v72
	v_log_f32_e32 v73, v73
	v_add_f32_e32 v68, 1.0, v88
	v_add_f32_e32 v69, 1.0, v89
	v_add_f32_e32 v70, 1.0, v86
	v_add_f32_e32 v71, 1.0, v87
	v_rcp_f32_e32 v90, v68
	v_mul_f32_e32 v74, s68, v72
	v_mul_f32_e32 v75, s68, v73
	v_mul_f32_e32 v72, s68, v84
	v_mul_f32_e32 v73, s68, v85
	v_rcp_f32_e32 v84, v70
	v_rcp_f32_e32 v91, v69
	v_rcp_f32_e32 v85, v71
	v_mul_f32_e32 v68, v76, v80
	v_mul_f32_e32 v69, v77, v81
	v_mul_f32_e32 v70, v78, v82
	v_mul_f32_e32 v71, v79, v83
	v_fma_f32 v76, v140, v90, v22
	v_fma_f32 v77, v141, v91, v23
	v_fma_f32 v78, v2, v84, v20
	v_fma_f32 v79, v3, v85, v21
	v_log_f32_e32 v76, v76
	v_log_f32_e32 v78, v78
	v_log_f32_e32 v77, v77
	v_log_f32_e32 v79, v79
	v_mul_f32_e32 v80, v144, v70
	v_mul_f32_e32 v81, v145, v71
	v_mul_f32_e32 v82, v142, v68
	v_mul_f32_e32 v83, v143, v69
	v_mul_f32_e32 v70, s68, v76
	v_mul_f32_e32 v71, s68, v77
	v_mul_f32_e32 v68, s68, v78
	v_mul_f32_e32 v69, s68, v79
	v_mul_f32_e32 v76, v86, v84
	v_mul_f32_e32 v77, v87, v85
	v_mul_f32_e32 v78, v88, v90
	v_mul_f32_e32 v79, v89, v91
	s_nop 0
	v_mul_f32_e32 v84, v140, v78
	v_mul_f32_e32 v85, v141, v79
	v_mul_f32_e32 v78, v2, v76
	v_mul_f32_e32 v79, v3, v77
	v_cvt_pk_bf16_f32 v76, v82, v83
	v_cvt_pk_bf16_f32 v77, v80, v81
	v_lshl_add_u64 v[80:81], s[30:31], 0, v[0:1]
	v_add_co_u32_e32 v80, vcc, 0x4400000, v80
	v_cvt_pk_bf16_f32 v78, v78, v79
	v_cvt_pk_bf16_f32 v79, v84, v85
	s_nop 1
	v_addc_co_u32_e32 v81, vcc, 0, v81, vcc
	global_store_dwordx4 v[80:81], v[76:79], off
.LBB0_391:
	v_cvt_pk_bf16_f32 v72, v72, v73
	v_cvt_pk_bf16_f32 v73, v74, v75
	v_cvt_pk_bf16_f32 v74, v68, v69
	v_lshl_add_u64 v[68:69], s[30:31], 0, v[0:1]
	s_and_b64 vcc, exec, s[8:9]
	v_cvt_pk_bf16_f32 v75, v70, v71
	global_store_dwordx4 v[68:69], v[72:75], off
	s_cbranch_vccnz .LBB0_395
	v_mul_f32_e32 v68, s96, v66
	v_mul_f32_e32 v69, s96, v67
	v_mul_f32_e32 v70, s96, v64
	v_mul_f32_e32 v71, s96, v65
	v_exp_f32_e32 v68, v68
	v_exp_f32_e32 v70, v70
	v_exp_f32_e32 v71, v71
	v_exp_f32_e32 v69, v69
	v_add_f32_e32 v70, 1.0, v70
	v_add_f32_e32 v71, 1.0, v71
	v_add_f32_e32 v68, 1.0, v68
	v_add_f32_e32 v69, 1.0, v69
	v_rcp_f32_e32 v70, v70
	v_rcp_f32_e32 v71, v71
	v_rcp_f32_e32 v68, v68
	v_rcp_f32_e32 v69, v69
	v_mul_f32_e32 v64, v64, v70
	v_mul_f32_e32 v65, v65, v71
	v_mul_f32_e32 v70, s96, v60
	v_mul_f32_e32 v71, s96, v61
	v_mul_f32_e32 v66, v66, v68
	v_mul_f32_e32 v67, v67, v69
	v_mul_f32_e32 v68, s96, v62
	v_mul_f32_e32 v69, s96, v63
	v_exp_f32_e32 v70, v70
	v_exp_f32_e32 v71, v71
	v_exp_f32_e32 v68, v68
	v_exp_f32_e32 v69, v69
	v_add_f32_e32 v70, 1.0, v70
	v_add_f32_e32 v71, 1.0, v71
	s_nop 0
	v_rcp_f32_e32 v70, v70
	v_add_f32_e32 v68, 1.0, v68
	v_add_f32_e32 v69, 1.0, v69
	v_rcp_f32_e32 v71, v71
	v_rcp_f32_e32 v68, v68
	v_rcp_f32_e32 v69, v69
	v_mul_f32_e32 v60, v60, v70
	v_mul_f32_e32 v61, v61, v71
	v_mul_f32_e32 v62, v62, v68
	v_mul_f32_e32 v63, v63, v69
	s_and_b64 vcc, exec, s[12:13]
	s_cbranch_vccz .LBB0_396

; __device__ __forceinline__ f32x4 silu4(f32x4 v) { return v * sigm4(v); }
; __device__ __forceinline__ u32x4 pack8(f32x4 v0, f32x4 v1) { u32x4 w; w.x = cvt_pk_bf16(v0[0], v0[1]); w.y = cvt_pk_bf16(v0[2], v0[3]); w.z = cvt_pk_bf16(v1[0], v1[1]); w.w = cvt_pk_bf16(v1[2], v1[3]); return w; }
; __device__ __forceinline__ void hg_gate4(f32x4& z, f32x4& key, const f32x4 l) {
;     const f32x4 zc = {__builtin_amdgcn_fmed3f(z[0], -80.f, 80.f), __builtin_amdgcn_fmed3f(z[1], -80.f, 80.f), __builtin_amdgcn_fmed3f(z[2], -80.f, 80.f), __builtin_amdgcn_fmed3f(z[3], -80.f, 80.f)};
;     const f32x4 t = zc * -1.4426950408889634f;
;     const f32x4 e = {__builtin_amdgcn_exp2f(t[0]), __builtin_amdgcn_exp2f(t[1]), __builtin_amdgcn_exp2f(t[2]), __builtin_amdgcn_exp2f(t[3])};
;     const f32x4 den = e + 1.0f;
;     const f32x4 sg = {__builtin_amdgcn_rcpf(den[0]), __builtin_amdgcn_rcpf(den[1]), __builtin_amdgcn_rcpf(den[2]), __builtin_amdgcn_rcpf(den[3])};
;     const f32x4 oml = 1.0f - l;
;     const f32x4 f = l + oml * sg;
;     z = (f32x4){__builtin_amdgcn_logf(f[0]), __builtin_amdgcn_logf(f[1]), __builtin_amdgcn_logf(f[2]), __builtin_amdgcn_logf(f[3])} * 0.6931471805599453f;
;     key = oml * (e * sg);
; }
;     __device__ __forceinline__ void operator()(const f32x4 (&acc)[2][2][4][2], const Unit& u, int wr, int wc, int fr_in, int fq_in) const {
;     ...
;                 for (int bj = 0; bj < 2; ++bj) {
;                     f32x4 v0 = acc[ai][bj][m][0], v1 = acc[ai][bj][m][1];
;                     if (type == 0) { v0 = silu4(v0); v1 = silu4(v1); }
;                     if (type == 4) { v0 = sigm4(v0); v1 = sigm4(v1); }
;                     if (type == 1 || type == 2) {
;                         f32x4 k0, k1;
;                         hg_gate4(v0, k0, lbv[bj][0]); hg_gate4(v1, k1, lbv[bj][1]);
;                         st16(base + tstride, roff + bj * HALF, pack8(k0, k1));
;                     }
;                     st16(base, roff + bj * HALF, pack8(v0, v1));
.LBB0_396:
	v_mul_f32_e32 v66, s96, v66
	v_mul_f32_e32 v67, s96, v67
	v_mul_f32_e32 v64, s96, v64
	v_mul_f32_e32 v65, s96, v65
	v_mul_f32_e32 v62, s96, v62
	v_mul_f32_e32 v63, s96, v63
	v_mul_f32_e32 v60, s96, v60
	v_mul_f32_e32 v61, s96, v61
	v_exp_f32_e32 v64, v64
	v_exp_f32_e32 v65, v65
	v_exp_f32_e32 v66, v66
	v_exp_f32_e32 v67, v67
	v_exp_f32_e32 v60, v60
	v_exp_f32_e32 v61, v61
	v_exp_f32_e32 v62, v62
	v_exp_f32_e32 v63, v63
	v_add_f32_e32 v66, 1.0, v66
	v_add_f32_e32 v67, 1.0, v67
	v_add_f32_e32 v64, 1.0, v64
	v_add_f32_e32 v65, 1.0, v65
	v_add_f32_e32 v60, 1.0, v60
	v_add_f32_e32 v61, 1.0, v61
	v_add_f32_e32 v62, 1.0, v62
	v_add_f32_e32 v63, 1.0, v63
	v_rcp_f32_e32 v64, v64
	v_rcp_f32_e32 v65, v65
	v_rcp_f32_e32 v66, v66
	v_rcp_f32_e32 v67, v67
	v_rcp_f32_e32 v60, v60
	v_rcp_f32_e32 v61, v61
	v_rcp_f32_e32 v62, v62
	v_rcp_f32_e32 v63, v63
	v_mov_b32_e32 v0, 0x90000
	s_and_b64 vcc, exec, s[10:11]
	v_lshl_add_u32 v0, v132, 1, v0
	s_cbranch_vccz .LBB0_394
.LBB0_397:
.LBB0_398:
	v_med3_f32 v64, v64, s95, v182
	v_med3_f32 v65, v65, s95, v182
	v_med3_f32 v66, v66, s95, v182
	v_med3_f32 v67, v67, s95, v182
	v_mul_f32_e32 v66, s96, v66
	v_mul_f32_e32 v67, s96, v67
	v_mul_f32_e32 v64, s96, v64
	v_mul_f32_e32 v65, s96, v65
	v_exp_f32_e32 v70, v66
	v_exp_f32_e32 v68, v64
	v_exp_f32_e32 v71, v67
	v_exp_f32_e32 v69, v65
	v_med3_f32 v60, v60, s95, v182
	v_med3_f32 v61, v61, s95, v182
	v_add_f32_e32 v64, 1.0, v70
	v_add_f32_e32 v65, 1.0, v71
	v_add_f32_e32 v66, 1.0, v68
	v_add_f32_e32 v67, 1.0, v69
	v_rcp_f32_e32 v74, v64
	v_rcp_f32_e32 v72, v66
	v_rcp_f32_e32 v75, v65
	v_rcp_f32_e32 v73, v67
	v_med3_f32 v62, v62, s95, v182
	v_med3_f32 v63, v63, s95, v182
	v_mul_f32_e32 v62, s96, v62
	v_mul_f32_e32 v63, s96, v63
	v_mul_f32_e32 v60, s96, v60
	v_mul_f32_e32 v61, s96, v61
	v_fma_f32 v64, v154, v74, v50
	v_fma_f32 v65, v155, v75, v51
	v_fma_f32 v66, v152, v72, v48
	v_fma_f32 v67, v153, v73, v49
	v_exp_f32_e32 v78, v60
	v_exp_f32_e32 v80, v62
	v_exp_f32_e32 v81, v63
	v_exp_f32_e32 v79, v61
	v_log_f32_e32 v76, v66
	v_log_f32_e32 v77, v67
	v_log_f32_e32 v64, v64
	v_log_f32_e32 v65, v65
	v_add_f32_e32 v60, 1.0, v80
	v_add_f32_e32 v61, 1.0, v81
	v_add_f32_e32 v62, 1.0, v78
	v_add_f32_e32 v63, 1.0, v79
	v_rcp_f32_e32 v82, v60
	v_mul_f32_e32 v66, s68, v64
	v_mul_f32_e32 v67, s68, v65
	v_mul_f32_e32 v64, s68, v76
	v_mul_f32_e32 v65, s68, v77
	v_rcp_f32_e32 v76, v62
	v_rcp_f32_e32 v83, v61
	v_rcp_f32_e32 v77, v63
	v_mul_f32_e32 v60, v68, v72
	v_mul_f32_e32 v61, v69, v73
	v_mul_f32_e32 v62, v70, v74
	v_mul_f32_e32 v63, v71, v75
	v_fma_f32 v68, v150, v82, v38
	v_fma_f32 v69, v151, v83, v39
	v_fma_f32 v70, v148, v76, v36
	v_fma_f32 v71, v149, v77, v37
	v_log_f32_e32 v68, v68
	v_log_f32_e32 v70, v70
	v_log_f32_e32 v69, v69
	v_log_f32_e32 v71, v71
	v_mul_f32_e32 v72, v154, v62
	v_mul_f32_e32 v73, v155, v63
	v_mul_f32_e32 v74, v152, v60
	v_mul_f32_e32 v75, v153, v61
	v_mul_f32_e32 v62, s68, v68
	v_mul_f32_e32 v63, s68, v69
	v_mul_f32_e32 v60, s68, v70
	v_mul_f32_e32 v61, s68, v71
	v_mul_f32_e32 v68, v78, v76
	v_mul_f32_e32 v69, v79, v77
	v_mul_f32_e32 v70, v80, v82
	v_mul_f32_e32 v71, v81, v83
	s_nop 0
	v_mul_f32_e32 v76, v150, v70
	v_mul_f32_e32 v77, v151, v71
	v_mul_f32_e32 v70, v148, v68
	v_mul_f32_e32 v71, v149, v69
	v_cvt_pk_bf16_f32 v68, v74, v75
	v_cvt_pk_bf16_f32 v69, v72, v73
	v_lshl_add_u64 v[72:73], s[30:31], 0, v[0:1]
	v_add_co_u32_e32 v72, vcc, 0x4400000, v72
	v_cvt_pk_bf16_f32 v70, v70, v71
	v_cvt_pk_bf16_f32 v71, v76, v77
	s_nop 1
	v_addc_co_u32_e32 v73, vcc, 0, v73, vcc
	global_store_dwordx4 v[72:73], v[68:71], off
.LBB0_399:
	v_cvt_pk_bf16_f32 v64, v64, v65
	v_cvt_pk_bf16_f32 v65, v66, v67
	v_cvt_pk_bf16_f32 v66, v60, v61
	v_lshl_add_u64 v[60:61], s[30:31], 0, v[0:1]
	s_and_b64 vcc, exec, s[8:9]
	v_cvt_pk_bf16_f32 v67, v62, v63
	global_store_dwordx4 v[60:61], v[64:67], off
	s_cbranch_vccnz .LBB0_403
	v_mul_f32_e32 v60, s96, v58
	v_mul_f32_e32 v61, s96, v59
	v_mul_f32_e32 v62, s96, v56
	v_mul_f32_e32 v63, s96, v57
	v_exp_f32_e32 v60, v60
	v_exp_f32_e32 v62, v62
	v_exp_f32_e32 v63, v63
	v_exp_f32_e32 v61, v61
	v_add_f32_e32 v62, 1.0, v62
	v_add_f32_e32 v63, 1.0, v63
	v_add_f32_e32 v60, 1.0, v60
	v_add_f32_e32 v61, 1.0, v61
	v_rcp_f32_e32 v62, v62
	v_rcp_f32_e32 v63, v63
	v_rcp_f32_e32 v60, v60
	v_rcp_f32_e32 v61, v61
	v_mul_f32_e32 v56, v56, v62
	v_mul_f32_e32 v57, v57, v63
	v_mul_f32_e32 v62, s96, v52
	v_mul_f32_e32 v63, s96, v53
	v_mul_f32_e32 v58, v58, v60
	v_mul_f32_e32 v59, v59, v61
	v_mul_f32_e32 v60, s96, v54
	v_mul_f32_e32 v61, s96, v55
	v_exp_f32_e32 v62, v62
	v_exp_f32_e32 v63, v63
	v_exp_f32_e32 v60, v60
	v_exp_f32_e32 v61, v61
	v_add_f32_e32 v62, 1.0, v62
	v_add_f32_e32 v63, 1.0, v63
	s_nop 0
	v_rcp_f32_e32 v62, v62
	v_add_f32_e32 v60, 1.0, v60
	v_add_f32_e32 v61, 1.0, v61
	v_rcp_f32_e32 v63, v63
	v_rcp_f32_e32 v60, v60
	v_rcp_f32_e32 v61, v61
	v_mul_f32_e32 v52, v52, v62
	v_mul_f32_e32 v53, v53, v63
	v_mul_f32_e32 v54, v54, v60
	v_mul_f32_e32 v55, v55, v61
	s_and_b64 vcc, exec, s[12:13]
	s_cbranch_vccz .LBB0_404

; __device__ __forceinline__ f32x4 sigm4(f32x4 v) { const f32x4 t = v * -1.4426950408889634f; f32x4 e = {__builtin_amdgcn_exp2f(t[0]), __builtin_amdgcn_exp2f(t[1]), __builtin_amdgcn_exp2f(t[2]), __builtin_amdgcn_exp2f(t[3])};
;     e = e + 1.0f; return (f32x4){__builtin_amdgcn_rcpf(e[0]), __builtin_amdgcn_rcpf(e[1]), __builtin_amdgcn_rcpf(e[2]), __builtin_amdgcn_rcpf(e[3])}; }
;     __device__ __forceinline__ void operator()(const f32x4 (&acc)[2][2][4][2], const Unit& u, int wr, int wc, int fr_in, int fq_in) const {
;     ...
;                     if (type == 4) { v0 = sigm4(v0); v1 = sigm4(v1); }
.LBB0_404:
	v_mul_f32_e32 v58, s96, v58
	v_mul_f32_e32 v59, s96, v59
	v_mul_f32_e32 v56, s96, v56
	v_mul_f32_e32 v57, s96, v57
	v_mul_f32_e32 v54, s96, v54
	v_mul_f32_e32 v55, s96, v55
	v_mul_f32_e32 v52, s96, v52
	v_mul_f32_e32 v53, s96, v53
	v_exp_f32_e32 v56, v56
	v_exp_f32_e32 v57, v57
	v_exp_f32_e32 v58, v58
	v_exp_f32_e32 v59, v59
	v_exp_f32_e32 v52, v52
	v_exp_f32_e32 v53, v53
	v_exp_f32_e32 v54, v54
	v_exp_f32_e32 v55, v55
	v_add_f32_e32 v58, 1.0, v58
	v_add_f32_e32 v59, 1.0, v59
	v_add_f32_e32 v56, 1.0, v56
	v_add_f32_e32 v57, 1.0, v57
	v_add_f32_e32 v52, 1.0, v52
	v_add_f32_e32 v53, 1.0, v53
	v_add_f32_e32 v54, 1.0, v54
	v_add_f32_e32 v55, 1.0, v55
	v_rcp_f32_e32 v56, v56
	v_rcp_f32_e32 v57, v57
	v_rcp_f32_e32 v58, v58
	v_rcp_f32_e32 v59, v59
	v_rcp_f32_e32 v52, v52
	v_rcp_f32_e32 v53, v53
	v_rcp_f32_e32 v54, v54
	v_rcp_f32_e32 v55, v55
	s_mov_b64 s[34:35], -1
	s_and_b64 vcc, exec, s[10:11]
	v_add_u32_e32 v0, 0x100, v0
	s_cbranch_vccz .LBB0_402

; __device__ __forceinline__ u32x4 pack8(f32x4 v0, f32x4 v1) { u32x4 w; w.x = cvt_pk_bf16(v0[0], v0[1]); w.y = cvt_pk_bf16(v0[2], v0[3]); w.z = cvt_pk_bf16(v1[0], v1[1]); w.w = cvt_pk_bf16(v1[2], v1[3]); return w; }
; __device__ __forceinline__ void hg_gate4(f32x4& z, f32x4& key, const f32x4 l) {
;     const f32x4 zc = {__builtin_amdgcn_fmed3f(z[0], -80.f, 80.f), __builtin_amdgcn_fmed3f(z[1], -80.f, 80.f), __builtin_amdgcn_fmed3f(z[2], -80.f, 80.f), __builtin_amdgcn_fmed3f(z[3], -80.f, 80.f)};
;     const f32x4 t = zc * -1.4426950408889634f;
;     const f32x4 e = {__builtin_amdgcn_exp2f(t[0]), __builtin_amdgcn_exp2f(t[1]), __builtin_amdgcn_exp2f(t[2]), __builtin_amdgcn_exp2f(t[3])};
;     const f32x4 den = e + 1.0f;
;     const f32x4 sg = {__builtin_amdgcn_rcpf(den[0]), __builtin_amdgcn_rcpf(den[1]), __builtin_amdgcn_rcpf(den[2]), __builtin_amdgcn_rcpf(den[3])};
;     const f32x4 oml = 1.0f - l;
;     const f32x4 f = l + oml * sg;
;     z = (f32x4){__builtin_amdgcn_logf(f[0]), __builtin_amdgcn_logf(f[1]), __builtin_amdgcn_logf(f[2]), __builtin_amdgcn_logf(f[3])} * 0.6931471805599453f;
;     key = oml * (e * sg);
; }
;     __device__ __forceinline__ void operator()(const f32x4 (&acc)[2][2][4][2], const Unit& u, int wr, int wc, int fr_in, int fq_in) const {
;     ...
;                     if (type == 1 || type == 2) {
;                         f32x4 k0, k1;
;                         hg_gate4(v0, k0, lbv[bj][0]); hg_gate4(v1, k1, lbv[bj][1]);
;                         st16(base + tstride, roff + bj * HALF, pack8(k0, k1));
;                     }
;                     st16(base, roff + bj * HALF, pack8(v0, v1));
.LBB0_406:
	v_med3_f32 v56, v56, s95, v182
	v_med3_f32 v57, v57, s95, v182
	v_med3_f32 v58, v58, s95, v182
	v_med3_f32 v59, v59, s95, v182
	v_mul_f32_e32 v58, s96, v58
	v_mul_f32_e32 v59, s96, v59
	v_mul_f32_e32 v56, s96, v56
	v_mul_f32_e32 v57, s96, v57
	v_exp_f32_e32 v62, v58
	v_exp_f32_e32 v60, v56
	v_exp_f32_e32 v63, v59
	v_exp_f32_e32 v61, v57
	v_med3_f32 v52, v52, s95, v182
	v_med3_f32 v53, v53, s95, v182
	v_add_f32_e32 v56, 1.0, v62
	v_add_f32_e32 v57, 1.0, v63
	v_add_f32_e32 v58, 1.0, v60
	v_add_f32_e32 v59, 1.0, v61
	v_rcp_f32_e32 v66, v56
	v_rcp_f32_e32 v64, v58
	v_rcp_f32_e32 v67, v57
	v_rcp_f32_e32 v65, v59
	v_med3_f32 v54, v54, s95, v182
	v_med3_f32 v55, v55, s95, v182
	v_mul_f32_e32 v54, s96, v54
	v_mul_f32_e32 v55, s96, v55
	v_mul_f32_e32 v52, s96, v52
	v_mul_f32_e32 v53, s96, v53
	v_fma_f32 v56, v144, v66, v26
	v_fma_f32 v57, v145, v67, v27
	v_fma_f32 v58, v142, v64, v24
	v_fma_f32 v59, v143, v65, v25
	v_exp_f32_e32 v70, v52
	v_exp_f32_e32 v72, v54
	v_exp_f32_e32 v73, v55
	v_exp_f32_e32 v71, v53
	v_log_f32_e32 v68, v58
	v_log_f32_e32 v69, v59
	v_log_f32_e32 v56, v56
	v_log_f32_e32 v57, v57
	v_add_f32_e32 v52, 1.0, v72
	v_add_f32_e32 v53, 1.0, v73
	v_add_f32_e32 v54, 1.0, v70
	v_add_f32_e32 v55, 1.0, v71
	v_rcp_f32_e32 v74, v52
	v_mul_f32_e32 v58, s68, v56
	v_mul_f32_e32 v59, s68, v57
	v_mul_f32_e32 v56, s68, v68
	v_mul_f32_e32 v57, s68, v69
	v_rcp_f32_e32 v68, v54
	v_rcp_f32_e32 v75, v53
	v_rcp_f32_e32 v69, v55
	v_mul_f32_e32 v52, v60, v64
	v_mul_f32_e32 v53, v61, v65
	v_mul_f32_e32 v54, v62, v66
	v_mul_f32_e32 v55, v63, v67
	v_fma_f32 v60, v140, v74, v22
	v_fma_f32 v61, v141, v75, v23
	v_fma_f32 v62, v2, v68, v20
	v_fma_f32 v63, v3, v69, v21
	v_log_f32_e32 v60, v60
	v_log_f32_e32 v62, v62
	v_log_f32_e32 v61, v61
	v_log_f32_e32 v63, v63
	v_mul_f32_e32 v64, v144, v54
	v_mul_f32_e32 v65, v145, v55
	v_mul_f32_e32 v66, v142, v52
	v_mul_f32_e32 v67, v143, v53
	v_mul_f32_e32 v54, s68, v60
	v_mul_f32_e32 v55, s68, v61
	v_mul_f32_e32 v52, s68, v62
	v_mul_f32_e32 v53, s68, v63
	v_mul_f32_e32 v60, v70, v68
	v_mul_f32_e32 v61, v71, v69
	v_mul_f32_e32 v62, v72, v74
	v_mul_f32_e32 v63, v73, v75
	s_nop 0
	v_mul_f32_e32 v68, v140, v62
	v_mul_f32_e32 v69, v141, v63
	v_mul_f32_e32 v62, v2, v60
	v_mul_f32_e32 v63, v3, v61
	v_cvt_pk_bf16_f32 v60, v66, v67
	v_cvt_pk_bf16_f32 v61, v64, v65
	v_lshl_add_u64 v[64:65], s[30:31], 0, v[0:1]
	v_add_co_u32_e32 v64, vcc, 0x4400000, v64
	v_cvt_pk_bf16_f32 v62, v62, v63
	v_cvt_pk_bf16_f32 v63, v68, v69
	s_nop 1
	v_addc_co_u32_e32 v65, vcc, 0, v65, vcc
	global_store_dwordx4 v[64:65], v[60:63], off
.LBB0_407:
	v_cvt_pk_bf16_f32 v56, v56, v57
	v_cvt_pk_bf16_f32 v57, v58, v59
	v_cvt_pk_bf16_f32 v58, v52, v53
	v_lshl_add_u64 v[52:53], s[30:31], 0, v[0:1]
	s_and_b64 vcc, exec, s[8:9]
	v_cvt_pk_bf16_f32 v59, v54, v55
	global_store_dwordx4 v[52:53], v[56:59], off
	s_cbranch_vccnz .LBB0_411
	v_mul_f32_e32 v52, s96, v46
	v_mul_f32_e32 v53, s96, v47
	v_mul_f32_e32 v54, s96, v44
	v_mul_f32_e32 v55, s96, v45
	v_exp_f32_e32 v52, v52
	v_exp_f32_e32 v54, v54
	v_exp_f32_e32 v55, v55
	v_exp_f32_e32 v53, v53
	v_add_f32_e32 v54, 1.0, v54
	v_add_f32_e32 v55, 1.0, v55
	v_add_f32_e32 v52, 1.0, v52
	v_add_f32_e32 v53, 1.0, v53
	v_rcp_f32_e32 v54, v54
	v_rcp_f32_e32 v55, v55
	v_rcp_f32_e32 v52, v52
	v_rcp_f32_e32 v53, v53
	v_mul_f32_e32 v44, v44, v54
	v_mul_f32_e32 v45, v45, v55
	v_mul_f32_e32 v54, s96, v40
	v_mul_f32_e32 v55, s96, v41
	v_mul_f32_e32 v46, v46, v52
	v_mul_f32_e32 v47, v47, v53
	v_mul_f32_e32 v52, s96, v42
	v_mul_f32_e32 v53, s96, v43
	v_exp_f32_e32 v54, v54
	v_exp_f32_e32 v55, v55
	v_exp_f32_e32 v52, v52
	v_exp_f32_e32 v53, v53
	v_add_f32_e32 v54, 1.0, v54
	v_add_f32_e32 v55, 1.0, v55
	s_nop 0
	v_rcp_f32_e32 v54, v54
	v_add_f32_e32 v52, 1.0, v52
	v_add_f32_e32 v53, 1.0, v53
	v_rcp_f32_e32 v55, v55
	v_rcp_f32_e32 v52, v52
	v_rcp_f32_e32 v53, v53
	v_mul_f32_e32 v40, v40, v54
	v_mul_f32_e32 v41, v41, v55
	v_mul_f32_e32 v42, v42, v52
	v_mul_f32_e32 v43, v43, v53
	s_and_b64 vcc, exec, s[12:13]
	s_cbranch_vccz .LBB0_412

; __device__ __forceinline__ f32x4 silu4(f32x4 v) { return v * sigm4(v); }
; __device__ __forceinline__ u32x4 pack8(f32x4 v0, f32x4 v1) { u32x4 w; w.x = cvt_pk_bf16(v0[0], v0[1]); w.y = cvt_pk_bf16(v0[2], v0[3]); w.z = cvt_pk_bf16(v1[0], v1[1]); w.w = cvt_pk_bf16(v1[2], v1[3]); return w; }
; __device__ __forceinline__ void hg_gate4(f32x4& z, f32x4& key, const f32x4 l) {
;     const f32x4 zc = {__builtin_amdgcn_fmed3f(z[0], -80.f, 80.f), __builtin_amdgcn_fmed3f(z[1], -80.f, 80.f), __builtin_amdgcn_fmed3f(z[2], -80.f, 80.f), __builtin_amdgcn_fmed3f(z[3], -80.f, 80.f)};
;     const f32x4 t = zc * -1.4426950408889634f;
;     const f32x4 e = {__builtin_amdgcn_exp2f(t[0]), __builtin_amdgcn_exp2f(t[1]), __builtin_amdgcn_exp2f(t[2]), __builtin_amdgcn_exp2f(t[3])};
;     const f32x4 den = e + 1.0f;
;     const f32x4 sg = {__builtin_amdgcn_rcpf(den[0]), __builtin_amdgcn_rcpf(den[1]), __builtin_amdgcn_rcpf(den[2]), __builtin_amdgcn_rcpf(den[3])};
;     const f32x4 oml = 1.0f - l;
;     const f32x4 f = l + oml * sg;
;     z = (f32x4){__builtin_amdgcn_logf(f[0]), __builtin_amdgcn_logf(f[1]), __builtin_amdgcn_logf(f[2]), __builtin_amdgcn_logf(f[3])} * 0.6931471805599453f;
;     key = oml * (e * sg);
; }
;     __device__ __forceinline__ void operator()(const f32x4 (&acc)[2][2][4][2], const Unit& u, int wr, int wc, int fr_in, int fq_in) const {
;     ...
;                 for (int bj = 0; bj < 2; ++bj) {
;                     f32x4 v0 = acc[ai][bj][m][0], v1 = acc[ai][bj][m][1];
;                     if (type == 0) { v0 = silu4(v0); v1 = silu4(v1); }
;                     if (type == 4) { v0 = sigm4(v0); v1 = sigm4(v1); }
;                     if (type == 1 || type == 2) {
;                         f32x4 k0, k1;
;                         hg_gate4(v0, k0, lbv[bj][0]); hg_gate4(v1, k1, lbv[bj][1]);
;                         st16(base + tstride, roff + bj * HALF, pack8(k0, k1));
;                     }
;                     st16(base, roff + bj * HALF, pack8(v0, v1));
.LBB0_412:
	v_mul_f32_e32 v46, s96, v46
	v_mul_f32_e32 v47, s96, v47
	v_mul_f32_e32 v44, s96, v44
	v_mul_f32_e32 v45, s96, v45
	v_mul_f32_e32 v42, s96, v42
	v_mul_f32_e32 v43, s96, v43
	v_mul_f32_e32 v40, s96, v40
	v_mul_f32_e32 v41, s96, v41
	v_exp_f32_e32 v44, v44
	v_exp_f32_e32 v45, v45
	v_exp_f32_e32 v46, v46
	v_exp_f32_e32 v47, v47
	v_exp_f32_e32 v40, v40
	v_exp_f32_e32 v41, v41
	v_exp_f32_e32 v42, v42
	v_exp_f32_e32 v43, v43
	v_add_f32_e32 v46, 1.0, v46
	v_add_f32_e32 v47, 1.0, v47
	v_add_f32_e32 v44, 1.0, v44
	v_add_f32_e32 v45, 1.0, v45
	v_add_f32_e32 v40, 1.0, v40
	v_add_f32_e32 v41, 1.0, v41
	v_add_f32_e32 v42, 1.0, v42
	v_add_f32_e32 v43, 1.0, v43
	v_rcp_f32_e32 v44, v44
	v_rcp_f32_e32 v45, v45
	v_rcp_f32_e32 v46, v46
	v_rcp_f32_e32 v47, v47
	v_rcp_f32_e32 v40, v40
	v_rcp_f32_e32 v41, v41
	v_rcp_f32_e32 v42, v42
	v_rcp_f32_e32 v43, v43
	v_mov_b32_e32 v0, 0xa0000
	s_and_b64 vcc, exec, s[10:11]
	v_lshl_add_u32 v0, v132, 1, v0
	s_cbranch_vccz .LBB0_410
.LBB0_413:
.LBB0_414:
	v_med3_f32 v44, v44, s95, v182
	v_med3_f32 v45, v45, s95, v182
	v_med3_f32 v46, v46, s95, v182
	v_med3_f32 v47, v47, s95, v182
	v_mul_f32_e32 v46, s96, v46
	v_mul_f32_e32 v47, s96, v47
	v_mul_f32_e32 v44, s96, v44
	v_mul_f32_e32 v45, s96, v45
	v_exp_f32_e32 v54, v46
	v_exp_f32_e32 v52, v44
	v_exp_f32_e32 v55, v47
	v_exp_f32_e32 v53, v45
	v_med3_f32 v40, v40, s95, v182
	v_med3_f32 v41, v41, s95, v182
	v_add_f32_e32 v44, 1.0, v54
	v_add_f32_e32 v45, 1.0, v55
	v_add_f32_e32 v46, 1.0, v52
	v_add_f32_e32 v47, 1.0, v53
	v_rcp_f32_e32 v58, v44
	v_rcp_f32_e32 v56, v46
	v_rcp_f32_e32 v59, v45
	v_rcp_f32_e32 v57, v47
	v_med3_f32 v42, v42, s95, v182
	v_med3_f32 v43, v43, s95, v182
	v_mul_f32_e32 v42, s96, v42
	v_mul_f32_e32 v43, s96, v43
	v_mul_f32_e32 v40, s96, v40
	v_mul_f32_e32 v41, s96, v41
	v_fma_f32 v44, v154, v58, v50
	v_fma_f32 v45, v155, v59, v51
	v_fma_f32 v46, v152, v56, v48
	v_fma_f32 v47, v153, v57, v49
	v_exp_f32_e32 v62, v40
	v_exp_f32_e32 v64, v42
	v_exp_f32_e32 v65, v43
	v_exp_f32_e32 v63, v41
	v_log_f32_e32 v60, v46
	v_log_f32_e32 v61, v47
	v_log_f32_e32 v44, v44
	v_log_f32_e32 v45, v45
	v_add_f32_e32 v40, 1.0, v64
	v_add_f32_e32 v41, 1.0, v65
	v_add_f32_e32 v42, 1.0, v62
	v_add_f32_e32 v43, 1.0, v63
	v_rcp_f32_e32 v66, v40
	v_mul_f32_e32 v46, s68, v44
	v_mul_f32_e32 v47, s68, v45
	v_mul_f32_e32 v44, s68, v60
	v_mul_f32_e32 v45, s68, v61
	v_rcp_f32_e32 v60, v42
	v_rcp_f32_e32 v67, v41
	v_rcp_f32_e32 v61, v43
	v_mul_f32_e32 v40, v52, v56
	v_mul_f32_e32 v41, v53, v57
	v_mul_f32_e32 v42, v54, v58
	v_mul_f32_e32 v43, v55, v59
	v_fma_f32 v52, v150, v66, v38
	v_fma_f32 v53, v151, v67, v39
	v_fma_f32 v54, v148, v60, v36
	v_fma_f32 v55, v149, v61, v37
	v_log_f32_e32 v52, v52
	v_log_f32_e32 v54, v54
	v_log_f32_e32 v53, v53
	v_log_f32_e32 v55, v55
	v_mul_f32_e32 v56, v154, v42
	v_mul_f32_e32 v57, v155, v43
	v_mul_f32_e32 v58, v152, v40
	v_mul_f32_e32 v59, v153, v41
	v_mul_f32_e32 v42, s68, v52
	v_mul_f32_e32 v43, s68, v53
	v_mul_f32_e32 v40, s68, v54
	v_mul_f32_e32 v41, s68, v55
	v_mul_f32_e32 v52, v62, v60
	v_mul_f32_e32 v53, v63, v61
	v_mul_f32_e32 v54, v64, v66
	v_mul_f32_e32 v55, v65, v67
	s_nop 0
	v_mul_f32_e32 v60, v150, v54
	v_mul_f32_e32 v61, v151, v55
	v_mul_f32_e32 v54, v148, v52
	v_mul_f32_e32 v55, v149, v53
	v_cvt_pk_bf16_f32 v52, v58, v59
	v_cvt_pk_bf16_f32 v53, v56, v57
	v_lshl_add_u64 v[56:57], s[30:31], 0, v[0:1]
	v_add_co_u32_e32 v56, vcc, 0x4400000, v56
	v_cvt_pk_bf16_f32 v54, v54, v55
	v_cvt_pk_bf16_f32 v55, v60, v61
	s_nop 1
	v_addc_co_u32_e32 v57, vcc, 0, v57, vcc
	global_store_dwordx4 v[56:57], v[52:55], off
.LBB0_415:
	v_cvt_pk_bf16_f32 v44, v44, v45
	v_cvt_pk_bf16_f32 v45, v46, v47
	v_cvt_pk_bf16_f32 v46, v40, v41
	v_lshl_add_u64 v[40:41], s[30:31], 0, v[0:1]
	s_and_b64 vcc, exec, s[8:9]
	v_cvt_pk_bf16_f32 v47, v42, v43
	global_store_dwordx4 v[40:41], v[44:47], off
	s_cbranch_vccnz .LBB0_419
	v_mul_f32_e32 v40, s96, v34
	v_mul_f32_e32 v41, s96, v35
	v_mul_f32_e32 v42, s96, v32
	v_mul_f32_e32 v43, s96, v33
	v_exp_f32_e32 v40, v40
	v_exp_f32_e32 v42, v42
	v_exp_f32_e32 v43, v43
	v_exp_f32_e32 v41, v41
	v_add_f32_e32 v42, 1.0, v42
	v_add_f32_e32 v43, 1.0, v43
	v_add_f32_e32 v40, 1.0, v40
	v_add_f32_e32 v41, 1.0, v41
	v_rcp_f32_e32 v42, v42
	v_rcp_f32_e32 v43, v43
	v_rcp_f32_e32 v40, v40
	v_rcp_f32_e32 v41, v41
	v_mul_f32_e32 v32, v32, v42
	v_mul_f32_e32 v33, v33, v43
	v_mul_f32_e32 v42, s96, v28
	v_mul_f32_e32 v43, s96, v29
	v_mul_f32_e32 v34, v34, v40
	v_mul_f32_e32 v35, v35, v41
	v_mul_f32_e32 v40, s96, v30
	v_mul_f32_e32 v41, s96, v31
	v_exp_f32_e32 v42, v42
	v_exp_f32_e32 v43, v43
	v_exp_f32_e32 v40, v40
	v_exp_f32_e32 v41, v41
	v_add_f32_e32 v42, 1.0, v42
	v_add_f32_e32 v43, 1.0, v43
	s_nop 0
	v_rcp_f32_e32 v42, v42
	v_add_f32_e32 v40, 1.0, v40
	v_add_f32_e32 v41, 1.0, v41
	v_rcp_f32_e32 v43, v43
	v_rcp_f32_e32 v40, v40
	v_rcp_f32_e32 v41, v41
	v_mul_f32_e32 v28, v28, v42
	v_mul_f32_e32 v29, v29, v43
	v_mul_f32_e32 v30, v30, v40
	v_mul_f32_e32 v31, v31, v41
	s_and_b64 vcc, exec, s[12:13]
	s_cbranch_vccz .LBB0_420

; __device__ __forceinline__ f32x4 sigm4(f32x4 v) { const f32x4 t = v * -1.4426950408889634f; f32x4 e = {__builtin_amdgcn_exp2f(t[0]), __builtin_amdgcn_exp2f(t[1]), __builtin_amdgcn_exp2f(t[2]), __builtin_amdgcn_exp2f(t[3])};
;     e = e + 1.0f; return (f32x4){__builtin_amdgcn_rcpf(e[0]), __builtin_amdgcn_rcpf(e[1]), __builtin_amdgcn_rcpf(e[2]), __builtin_amdgcn_rcpf(e[3])}; }
;     __device__ __forceinline__ void operator()(const f32x4 (&acc)[2][2][4][2], const Unit& u, int wr, int wc, int fr_in, int fq_in) const {
;     ...
;                     if (type == 4) { v0 = sigm4(v0); v1 = sigm4(v1); }
.LBB0_420:
	v_mul_f32_e32 v34, s96, v34
	v_mul_f32_e32 v35, s96, v35
	v_mul_f32_e32 v32, s96, v32
	v_mul_f32_e32 v33, s96, v33
	v_mul_f32_e32 v30, s96, v30
	v_mul_f32_e32 v31, s96, v31
	v_mul_f32_e32 v28, s96, v28
	v_mul_f32_e32 v29, s96, v29
	v_exp_f32_e32 v32, v32
	v_exp_f32_e32 v33, v33
	v_exp_f32_e32 v34, v34
	v_exp_f32_e32 v35, v35
	v_exp_f32_e32 v28, v28
	v_exp_f32_e32 v29, v29
	v_exp_f32_e32 v30, v30
	v_exp_f32_e32 v31, v31
	v_add_f32_e32 v34, 1.0, v34
	v_add_f32_e32 v35, 1.0, v35
	v_add_f32_e32 v32, 1.0, v32
	v_add_f32_e32 v33, 1.0, v33
	v_add_f32_e32 v28, 1.0, v28
	v_add_f32_e32 v29, 1.0, v29
	v_add_f32_e32 v30, 1.0, v30
	v_add_f32_e32 v31, 1.0, v31
	v_rcp_f32_e32 v32, v32
	v_rcp_f32_e32 v33, v33
	v_rcp_f32_e32 v34, v34
	v_rcp_f32_e32 v35, v35
	v_rcp_f32_e32 v28, v28
	v_rcp_f32_e32 v29, v29
	v_rcp_f32_e32 v30, v30
	v_rcp_f32_e32 v31, v31
	s_mov_b64 s[34:35], -1
	s_and_b64 vcc, exec, s[10:11]
	v_add_u32_e32 v0, 0x100, v0
	s_cbranch_vccz .LBB0_418

; __device__ __forceinline__ u32x4 pack8(f32x4 v0, f32x4 v1) { u32x4 w; w.x = cvt_pk_bf16(v0[0], v0[1]); w.y = cvt_pk_bf16(v0[2], v0[3]); w.z = cvt_pk_bf16(v1[0], v1[1]); w.w = cvt_pk_bf16(v1[2], v1[3]); return w; }
; __device__ __forceinline__ void hg_gate4(f32x4& z, f32x4& key, const f32x4 l) {
;     const f32x4 zc = {__builtin_amdgcn_fmed3f(z[0], -80.f, 80.f), __builtin_amdgcn_fmed3f(z[1], -80.f, 80.f), __builtin_amdgcn_fmed3f(z[2], -80.f, 80.f), __builtin_amdgcn_fmed3f(z[3], -80.f, 80.f)};
;     const f32x4 t = zc * -1.4426950408889634f;
;     const f32x4 e = {__builtin_amdgcn_exp2f(t[0]), __builtin_amdgcn_exp2f(t[1]), __builtin_amdgcn_exp2f(t[2]), __builtin_amdgcn_exp2f(t[3])};
;     const f32x4 den = e + 1.0f;
;     const f32x4 sg = {__builtin_amdgcn_rcpf(den[0]), __builtin_amdgcn_rcpf(den[1]), __builtin_amdgcn_rcpf(den[2]), __builtin_amdgcn_rcpf(den[3])};
;     const f32x4 oml = 1.0f - l;
;     const f32x4 f = l + oml * sg;
;     z = (f32x4){__builtin_amdgcn_logf(f[0]), __builtin_amdgcn_logf(f[1]), __builtin_amdgcn_logf(f[2]), __builtin_amdgcn_logf(f[3])} * 0.6931471805599453f;
;     key = oml * (e * sg);
; }
;     __device__ __forceinline__ void operator()(const f32x4 (&acc)[2][2][4][2], const Unit& u, int wr, int wc, int fr_in, int fq_in) const {
;     ...
;                     if (type == 1 || type == 2) {
;                         f32x4 k0, k1;
;                         hg_gate4(v0, k0, lbv[bj][0]); hg_gate4(v1, k1, lbv[bj][1]);
;                         st16(base + tstride, roff + bj * HALF, pack8(k0, k1));
;                     }
;                     st16(base, roff + bj * HALF, pack8(v0, v1));
.LBB0_422:
	v_med3_f32 v32, v32, s95, v182
	v_med3_f32 v33, v33, s95, v182
	v_med3_f32 v34, v34, s95, v182
	v_med3_f32 v35, v35, s95, v182
	v_mul_f32_e32 v34, s96, v34
	v_mul_f32_e32 v35, s96, v35
	v_mul_f32_e32 v32, s96, v32
	v_mul_f32_e32 v33, s96, v33
	v_exp_f32_e32 v42, v34
	v_exp_f32_e32 v40, v32
	v_exp_f32_e32 v43, v35
	v_exp_f32_e32 v41, v33
	v_med3_f32 v28, v28, s95, v182
	v_med3_f32 v29, v29, s95, v182
	v_add_f32_e32 v32, 1.0, v42
	v_add_f32_e32 v33, 1.0, v43
	v_add_f32_e32 v34, 1.0, v40
	v_add_f32_e32 v35, 1.0, v41
	v_rcp_f32_e32 v46, v32
	v_rcp_f32_e32 v44, v34
	v_rcp_f32_e32 v47, v33
	v_rcp_f32_e32 v45, v35
	v_med3_f32 v30, v30, s95, v182
	v_med3_f32 v31, v31, s95, v182
	v_mul_f32_e32 v30, s96, v30
	v_mul_f32_e32 v31, s96, v31
	v_mul_f32_e32 v28, s96, v28
	v_mul_f32_e32 v29, s96, v29
	v_fma_f32 v32, v144, v46, v26
	v_fma_f32 v33, v145, v47, v27
	v_fma_f32 v34, v142, v44, v24
	v_fma_f32 v35, v143, v45, v25
	v_exp_f32_e32 v54, v28
	v_exp_f32_e32 v56, v30
	v_exp_f32_e32 v57, v31
	v_exp_f32_e32 v55, v29
	v_log_f32_e32 v52, v34
	v_log_f32_e32 v53, v35
	v_log_f32_e32 v32, v32
	v_log_f32_e32 v33, v33
	v_add_f32_e32 v28, 1.0, v56
	v_add_f32_e32 v29, 1.0, v57
	v_add_f32_e32 v30, 1.0, v54
	v_add_f32_e32 v31, 1.0, v55
	v_rcp_f32_e32 v58, v28
	v_mul_f32_e32 v34, s68, v32
	v_mul_f32_e32 v35, s68, v33
	v_mul_f32_e32 v32, s68, v52
	v_mul_f32_e32 v33, s68, v53
	v_rcp_f32_e32 v52, v30
	v_rcp_f32_e32 v59, v29
	v_rcp_f32_e32 v53, v31
	v_mul_f32_e32 v28, v40, v44
	v_mul_f32_e32 v29, v41, v45
	v_mul_f32_e32 v30, v42, v46
	v_mul_f32_e32 v31, v43, v47
	v_fma_f32 v40, v140, v58, v22
	v_fma_f32 v41, v141, v59, v23
	v_fma_f32 v42, v2, v52, v20
	v_fma_f32 v43, v3, v53, v21
	v_log_f32_e32 v40, v40
	v_log_f32_e32 v42, v42
	v_log_f32_e32 v41, v41
	v_log_f32_e32 v43, v43
	v_mul_f32_e32 v44, v144, v30
	v_mul_f32_e32 v45, v145, v31
	v_mul_f32_e32 v46, v142, v28
	v_mul_f32_e32 v47, v143, v29
	v_mul_f32_e32 v30, s68, v40
	v_mul_f32_e32 v31, s68, v41
	v_mul_f32_e32 v28, s68, v42
	v_mul_f32_e32 v29, s68, v43
	v_mul_f32_e32 v40, v54, v52
	v_mul_f32_e32 v41, v55, v53
	v_mul_f32_e32 v42, v56, v58
	v_mul_f32_e32 v43, v57, v59
	s_nop 0
	v_mul_f32_e32 v52, v140, v42
	v_mul_f32_e32 v53, v141, v43
	v_mul_f32_e32 v42, v2, v40
	v_mul_f32_e32 v43, v3, v41
	v_cvt_pk_bf16_f32 v40, v46, v47
	v_cvt_pk_bf16_f32 v41, v44, v45
	v_lshl_add_u64 v[44:45], s[30:31], 0, v[0:1]
	v_add_co_u32_e32 v44, vcc, 0x4400000, v44
	v_cvt_pk_bf16_f32 v42, v42, v43
	v_cvt_pk_bf16_f32 v43, v52, v53
	s_nop 1
	v_addc_co_u32_e32 v45, vcc, 0, v45, vcc
	global_store_dwordx4 v[44:45], v[40:43], off
.LBB0_423:
	v_cvt_pk_bf16_f32 v32, v32, v33
	v_cvt_pk_bf16_f32 v33, v34, v35
	v_cvt_pk_bf16_f32 v34, v28, v29
	v_lshl_add_u64 v[28:29], s[30:31], 0, v[0:1]
	s_and_b64 vcc, exec, s[8:9]
	v_cvt_pk_bf16_f32 v35, v30, v31
	global_store_dwordx4 v[28:29], v[32:35], off
	s_cbranch_vccnz .LBB0_427
	v_mul_f32_e32 v28, s96, v14
	v_mul_f32_e32 v29, s96, v15
	v_mul_f32_e32 v30, s96, v12
	v_mul_f32_e32 v31, s96, v13
	v_exp_f32_e32 v28, v28
	v_exp_f32_e32 v30, v30
	v_exp_f32_e32 v31, v31
	v_exp_f32_e32 v29, v29
	v_add_f32_e32 v30, 1.0, v30
	v_add_f32_e32 v31, 1.0, v31
	v_add_f32_e32 v28, 1.0, v28
	v_add_f32_e32 v29, 1.0, v29
	v_rcp_f32_e32 v30, v30
	v_rcp_f32_e32 v31, v31
	v_rcp_f32_e32 v28, v28
	v_rcp_f32_e32 v29, v29
	v_mul_f32_e32 v12, v12, v30
	v_mul_f32_e32 v13, v13, v31
	v_mul_f32_e32 v30, s96, v16
	v_mul_f32_e32 v31, s96, v17
	v_mul_f32_e32 v14, v14, v28
	v_mul_f32_e32 v15, v15, v29
	v_mul_f32_e32 v28, s96, v18
	v_mul_f32_e32 v29, s96, v19
	v_exp_f32_e32 v30, v30
	v_exp_f32_e32 v31, v31
	v_exp_f32_e32 v28, v28
	v_exp_f32_e32 v29, v29
	v_add_f32_e32 v30, 1.0, v30
	v_add_f32_e32 v31, 1.0, v31
	s_nop 0
	v_rcp_f32_e32 v30, v30
	v_add_f32_e32 v28, 1.0, v28
	v_add_f32_e32 v29, 1.0, v29
	v_rcp_f32_e32 v31, v31
	v_rcp_f32_e32 v28, v28
	v_rcp_f32_e32 v29, v29
	v_mul_f32_e32 v16, v16, v30
	v_mul_f32_e32 v17, v17, v31
	v_mul_f32_e32 v18, v18, v28
	v_mul_f32_e32 v19, v19, v29
	s_and_b64 vcc, exec, s[12:13]
	s_cbranch_vccz .LBB0_428

; __device__ __forceinline__ u32x4 pack8(f32x4 v0, f32x4 v1) { u32x4 w; w.x = cvt_pk_bf16(v0[0], v0[1]); w.y = cvt_pk_bf16(v0[2], v0[3]); w.z = cvt_pk_bf16(v1[0], v1[1]); w.w = cvt_pk_bf16(v1[2], v1[3]); return w; }
; __device__ __forceinline__ f32x4 sigm4(f32x4 v) { const f32x4 t = v * -1.4426950408889634f; f32x4 e = {__builtin_amdgcn_exp2f(t[0]), __builtin_amdgcn_exp2f(t[1]), __builtin_amdgcn_exp2f(t[2]), __builtin_amdgcn_exp2f(t[3])};
;     e = e + 1.0f; return (f32x4){__builtin_amdgcn_rcpf(e[0]), __builtin_amdgcn_rcpf(e[1]), __builtin_amdgcn_rcpf(e[2]), __builtin_amdgcn_rcpf(e[3])}; }
; __device__ __forceinline__ f32x4 silu4(f32x4 v) { return v * sigm4(v); }
; __device__ __forceinline__ void hg_gate4(f32x4& z, f32x4& key, const f32x4 l) {
;     const f32x4 zc = {__builtin_amdgcn_fmed3f(z[0], -80.f, 80.f), __builtin_amdgcn_fmed3f(z[1], -80.f, 80.f), __builtin_amdgcn_fmed3f(z[2], -80.f, 80.f), __builtin_amdgcn_fmed3f(z[3], -80.f, 80.f)};
;     const f32x4 t = zc * -1.4426950408889634f;
;     const f32x4 e = {__builtin_amdgcn_exp2f(t[0]), __builtin_amdgcn_exp2f(t[1]), __builtin_amdgcn_exp2f(t[2]), __builtin_amdgcn_exp2f(t[3])};
;     const f32x4 den = e + 1.0f;
;     const f32x4 sg = {__builtin_amdgcn_rcpf(den[0]), __builtin_amdgcn_rcpf(den[1]), __builtin_amdgcn_rcpf(den[2]), __builtin_amdgcn_rcpf(den[3])};
;     const f32x4 oml = 1.0f - l;
;     const f32x4 f = l + oml * sg;
;     z = (f32x4){__builtin_amdgcn_logf(f[0]), __builtin_amdgcn_logf(f[1]), __builtin_amdgcn_logf(f[2]), __builtin_amdgcn_logf(f[3])} * 0.6931471805599453f;
;     key = oml * (e * sg);
; }
;     __device__ __forceinline__ void operator()(const f32x4 (&acc)[2][2][4][2], const Unit& u, int wr, int wc, int fr_in, int fq_in) const {
;     ...
;                 for (int bj = 0; bj < 2; ++bj) {
;                     f32x4 v0 = acc[ai][bj][m][0], v1 = acc[ai][bj][m][1];
;                     if (type == 0) { v0 = silu4(v0); v1 = silu4(v1); }
;                     if (type == 4) { v0 = sigm4(v0); v1 = sigm4(v1); }
;                     if (type == 1 || type == 2) {
;                         f32x4 k0, k1;
;                         hg_gate4(v0, k0, lbv[bj][0]); hg_gate4(v1, k1, lbv[bj][1]);
;                         st16(base + tstride, roff + bj * HALF, pack8(k0, k1));
;                     }
;                     st16(base, roff + bj * HALF, pack8(v0, v1));
.LBB0_428:
	v_mul_f32_e32 v14, s96, v14
	v_mul_f32_e32 v15, s96, v15
	v_mul_f32_e32 v12, s96, v12
	v_mul_f32_e32 v13, s96, v13
	v_mul_f32_e32 v18, s96, v18
	v_mul_f32_e32 v19, s96, v19
	v_mul_f32_e32 v16, s96, v16
	v_mul_f32_e32 v17, s96, v17
	v_exp_f32_e32 v12, v12
	v_exp_f32_e32 v13, v13
	v_exp_f32_e32 v14, v14
	v_exp_f32_e32 v15, v15
	v_exp_f32_e32 v16, v16
	v_exp_f32_e32 v17, v17
	v_exp_f32_e32 v18, v18
	v_exp_f32_e32 v19, v19
	v_add_f32_e32 v14, 1.0, v14
	v_add_f32_e32 v15, 1.0, v15
	v_add_f32_e32 v12, 1.0, v12
	v_add_f32_e32 v13, 1.0, v13
	v_add_f32_e32 v16, 1.0, v16
	v_add_f32_e32 v17, 1.0, v17
	v_add_f32_e32 v18, 1.0, v18
	v_add_f32_e32 v19, 1.0, v19
	v_rcp_f32_e32 v12, v12
	v_rcp_f32_e32 v13, v13
	v_rcp_f32_e32 v14, v14
	v_rcp_f32_e32 v15, v15
	v_rcp_f32_e32 v16, v16
	v_rcp_f32_e32 v17, v17
	v_rcp_f32_e32 v18, v18
	v_rcp_f32_e32 v19, v19
	v_mov_b32_e32 v0, 0xb0000
	s_and_b64 vcc, exec, s[10:11]
	v_lshl_add_u32 v0, v132, 1, v0
	s_cbranch_vccz .LBB0_426
.LBB0_429:
.LBB0_430:
	v_med3_f32 v12, v12, s95, v182
	v_med3_f32 v13, v13, s95, v182
	v_med3_f32 v14, v14, s95, v182
	v_med3_f32 v15, v15, s95, v182
	v_mul_f32_e32 v14, s96, v14
	v_mul_f32_e32 v15, s96, v15
	v_mul_f32_e32 v12, s96, v12
	v_mul_f32_e32 v13, s96, v13
	v_exp_f32_e32 v30, v14
	v_exp_f32_e32 v28, v12
	v_exp_f32_e32 v29, v13
	v_exp_f32_e32 v31, v15
	v_med3_f32 v16, v16, s95, v182
	v_med3_f32 v17, v17, s95, v182
	v_add_f32_e32 v14, 1.0, v28
	v_add_f32_e32 v15, 1.0, v29
	v_add_f32_e32 v12, 1.0, v30
	v_add_f32_e32 v13, 1.0, v31
	v_rcp_f32_e32 v32, v14
	v_rcp_f32_e32 v33, v15
	v_rcp_f32_e32 v34, v12
	v_rcp_f32_e32 v35, v13
	v_med3_f32 v18, v18, s95, v182
	v_med3_f32 v19, v19, s95, v182
	v_mul_f32_e32 v18, s96, v18
	v_mul_f32_e32 v19, s96, v19
	v_mul_f32_e32 v16, s96, v16
	v_mul_f32_e32 v17, s96, v17
	v_fma_f32 v12, v154, v34, v50
	v_fma_f32 v13, v155, v35, v51
	v_fma_f32 v14, v152, v32, v48
	v_fma_f32 v15, v153, v33, v49
	v_mul_f32_e32 v28, v28, v32
	v_mul_f32_e32 v29, v29, v33
	v_mul_f32_e32 v30, v30, v34
	v_mul_f32_e32 v31, v31, v35
	v_exp_f32_e32 v32, v16
	v_exp_f32_e32 v33, v17
	v_exp_f32_e32 v34, v18
	v_exp_f32_e32 v35, v19
	v_log_f32_e32 v40, v14
	v_log_f32_e32 v41, v15
	v_log_f32_e32 v12, v12
	v_log_f32_e32 v13, v13
	v_add_f32_e32 v16, 1.0, v34
	v_add_f32_e32 v17, 1.0, v35
	v_add_f32_e32 v18, 1.0, v32
	v_add_f32_e32 v19, 1.0, v33
	v_rcp_f32_e32 v42, v16
	v_mul_f32_e32 v14, s68, v12
	v_mul_f32_e32 v15, s68, v13
	v_mul_f32_e32 v12, s68, v40
	v_mul_f32_e32 v13, s68, v41
	v_rcp_f32_e32 v40, v18
	v_rcp_f32_e32 v41, v19
	v_rcp_f32_e32 v43, v17
	v_mul_f32_e32 v30, v154, v30
	v_mul_f32_e32 v31, v155, v31
	v_mul_f32_e32 v28, v152, v28
	v_mul_f32_e32 v29, v153, v29
	v_fma_f32 v18, v148, v40, v36
	v_fma_f32 v19, v149, v41, v37
	v_fma_f32 v16, v150, v42, v38
	v_fma_f32 v17, v151, v43, v39
	v_log_f32_e32 v36, v18
	v_log_f32_e32 v37, v19
	v_log_f32_e32 v16, v16
	v_log_f32_e32 v17, v17
	v_mul_f32_e32 v32, v32, v40
	v_mul_f32_e32 v33, v33, v41
	v_cvt_pk_bf16_f32 v28, v28, v29
	v_cvt_pk_bf16_f32 v29, v30, v31
	v_mul_f32_e32 v18, s68, v16
	v_mul_f32_e32 v19, s68, v17
	v_mul_f32_e32 v32, v148, v32
	v_mul_f32_e32 v33, v149, v33
	v_mul_f32_e32 v16, s68, v36
	v_mul_f32_e32 v17, s68, v37
	v_cvt_pk_bf16_f32 v30, v32, v33
	v_lshl_add_u64 v[32:33], s[30:31], 0, v[0:1]
	v_add_co_u32_e32 v32, vcc, 0x4400000, v32
	v_mul_f32_e32 v34, v34, v42
	v_mul_f32_e32 v35, v35, v43
	s_nop 0
	v_addc_co_u32_e32 v33, vcc, 0, v33, vcc
	v_mul_f32_e32 v34, v150, v34
	v_mul_f32_e32 v35, v151, v35
	s_nop 0
	v_cvt_pk_bf16_f32 v31, v34, v35
	global_store_dwordx4 v[32:33], v[28:31], off
.LBB0_431:
	v_cvt_pk_bf16_f32 v12, v12, v13
	v_cvt_pk_bf16_f32 v13, v14, v15
	v_cvt_pk_bf16_f32 v14, v16, v17
	v_lshl_add_u64 v[16:17], s[30:31], 0, v[0:1]
	s_and_b64 vcc, exec, s[8:9]
	v_cvt_pk_bf16_f32 v15, v18, v19
	global_store_dwordx4 v[16:17], v[12:15], off
	s_cbranch_vccnz .LBB0_435
	s_nop 0
	v_mul_f32_e32 v12, s96, v6
	v_mul_f32_e32 v13, s96, v7
	v_mul_f32_e32 v14, s96, v4
	v_mul_f32_e32 v15, s96, v5
	v_exp_f32_e32 v12, v12
	v_exp_f32_e32 v14, v14
	v_exp_f32_e32 v15, v15
	v_exp_f32_e32 v13, v13
	v_add_f32_e32 v14, 1.0, v14
	v_add_f32_e32 v15, 1.0, v15
	v_add_f32_e32 v12, 1.0, v12
	v_add_f32_e32 v13, 1.0, v13
	v_rcp_f32_e32 v14, v14
	v_rcp_f32_e32 v15, v15
	v_rcp_f32_e32 v12, v12
	v_rcp_f32_e32 v13, v13
	v_mul_f32_e32 v4, v4, v14
	v_mul_f32_e32 v5, v5, v15
	v_mul_f32_e32 v14, s96, v8
	v_mul_f32_e32 v15, s96, v9
	v_mul_f32_e32 v6, v6, v12
	v_mul_f32_e32 v7, v7, v13
	v_mul_f32_e32 v12, s96, v10
	v_mul_f32_e32 v13, s96, v11
	v_exp_f32_e32 v14, v14
	v_exp_f32_e32 v15, v15
	v_exp_f32_e32 v12, v12
	v_exp_f32_e32 v13, v13
	v_add_f32_e32 v14, 1.0, v14
	v_add_f32_e32 v15, 1.0, v15
	s_nop 0
	v_rcp_f32_e32 v14, v14
	v_add_f32_e32 v12, 1.0, v12
	v_add_f32_e32 v13, 1.0, v13
	v_rcp_f32_e32 v15, v15
	v_rcp_f32_e32 v12, v12
	v_rcp_f32_e32 v13, v13
	v_mul_f32_e32 v8, v8, v14
	v_mul_f32_e32 v9, v9, v15
	v_mul_f32_e32 v10, v10, v12
	v_mul_f32_e32 v11, v11, v13
	s_and_b64 vcc, exec, s[12:13]
	s_cbranch_vccz .LBB0_436

; __device__ __forceinline__ f32x4 sigm4(f32x4 v) { const f32x4 t = v * -1.4426950408889634f; f32x4 e = {__builtin_amdgcn_exp2f(t[0]), __builtin_amdgcn_exp2f(t[1]), __builtin_amdgcn_exp2f(t[2]), __builtin_amdgcn_exp2f(t[3])};
;     e = e + 1.0f; return (f32x4){__builtin_amdgcn_rcpf(e[0]), __builtin_amdgcn_rcpf(e[1]), __builtin_amdgcn_rcpf(e[2]), __builtin_amdgcn_rcpf(e[3])}; }
;     __device__ __forceinline__ void operator()(const f32x4 (&acc)[2][2][4][2], const Unit& u, int wr, int wc, int fr_in, int fq_in) const {
;     ...
;                     if (type == 4) { v0 = sigm4(v0); v1 = sigm4(v1); }
.LBB0_436:
	v_mul_f32_e32 v6, s96, v6
	v_mul_f32_e32 v7, s96, v7
	v_mul_f32_e32 v4, s96, v4
	v_mul_f32_e32 v5, s96, v5
	v_mul_f32_e32 v10, s96, v10
	v_mul_f32_e32 v11, s96, v11
	v_mul_f32_e32 v8, s96, v8
	v_mul_f32_e32 v9, s96, v9
	v_exp_f32_e32 v4, v4
	v_exp_f32_e32 v5, v5
	v_exp_f32_e32 v6, v6
	v_exp_f32_e32 v7, v7
	v_exp_f32_e32 v8, v8
	v_exp_f32_e32 v9, v9
	v_exp_f32_e32 v10, v10
	v_exp_f32_e32 v11, v11
	v_add_f32_e32 v6, 1.0, v6
	v_add_f32_e32 v7, 1.0, v7
	v_add_f32_e32 v4, 1.0, v4
	v_add_f32_e32 v5, 1.0, v5
	v_add_f32_e32 v8, 1.0, v8
	v_add_f32_e32 v9, 1.0, v9
	v_add_f32_e32 v10, 1.0, v10
	v_add_f32_e32 v11, 1.0, v11
	v_rcp_f32_e32 v4, v4
	v_rcp_f32_e32 v5, v5
	v_rcp_f32_e32 v6, v6
	v_rcp_f32_e32 v7, v7
	v_rcp_f32_e32 v8, v8
	v_rcp_f32_e32 v9, v9
	v_rcp_f32_e32 v10, v10
	v_rcp_f32_e32 v11, v11
	s_mov_b64 s[8:9], -1
	s_and_b64 vcc, exec, s[10:11]
	v_add_u32_e32 v0, 0x100, v0
	s_cbranch_vccz .LBB0_434

; __device__ __forceinline__ u32x4 pack8(f32x4 v0, f32x4 v1) { u32x4 w; w.x = cvt_pk_bf16(v0[0], v0[1]); w.y = cvt_pk_bf16(v0[2], v0[3]); w.z = cvt_pk_bf16(v1[0], v1[1]); w.w = cvt_pk_bf16(v1[2], v1[3]); return w; }
; __device__ __forceinline__ void hg_gate4(f32x4& z, f32x4& key, const f32x4 l) {
;     const f32x4 zc = {__builtin_amdgcn_fmed3f(z[0], -80.f, 80.f), __builtin_amdgcn_fmed3f(z[1], -80.f, 80.f), __builtin_amdgcn_fmed3f(z[2], -80.f, 80.f), __builtin_amdgcn_fmed3f(z[3], -80.f, 80.f)};
;     const f32x4 t = zc * -1.4426950408889634f;
;     const f32x4 e = {__builtin_amdgcn_exp2f(t[0]), __builtin_amdgcn_exp2f(t[1]), __builtin_amdgcn_exp2f(t[2]), __builtin_amdgcn_exp2f(t[3])};
;     const f32x4 den = e + 1.0f;
;     const f32x4 sg = {__builtin_amdgcn_rcpf(den[0]), __builtin_amdgcn_rcpf(den[1]), __builtin_amdgcn_rcpf(den[2]), __builtin_amdgcn_rcpf(den[3])};
;     const f32x4 oml = 1.0f - l;
;     const f32x4 f = l + oml * sg;
;     z = (f32x4){__builtin_amdgcn_logf(f[0]), __builtin_amdgcn_logf(f[1]), __builtin_amdgcn_logf(f[2]), __builtin_amdgcn_logf(f[3])} * 0.6931471805599453f;
;     key = oml * (e * sg);
; }
;     __device__ __forceinline__ void operator()(const f32x4 (&acc)[2][2][4][2], const Unit& u, int wr, int wc, int fr_in, int fq_in) const {
;     ...
;                     if (type == 1 || type == 2) {
;                         f32x4 k0, k1;
;                         hg_gate4(v0, k0, lbv[bj][0]); hg_gate4(v1, k1, lbv[bj][1]);
;                         st16(base + tstride, roff + bj * HALF, pack8(k0, k1));
.LBB0_438:
	v_med3_f32 v4, v4, s95, v182
	v_med3_f32 v5, v5, s95, v182
	v_med3_f32 v6, v6, s95, v182
	v_med3_f32 v7, v7, s95, v182
	v_mul_f32_e32 v6, s96, v6
	v_mul_f32_e32 v7, s96, v7
	v_mul_f32_e32 v4, s96, v4
	v_mul_f32_e32 v5, s96, v5
	v_exp_f32_e32 v14, v6
	v_exp_f32_e32 v12, v4
	v_exp_f32_e32 v13, v5
	v_exp_f32_e32 v15, v7
	v_med3_f32 v8, v8, s95, v182
	v_med3_f32 v9, v9, s95, v182
	v_add_f32_e32 v6, 1.0, v12
	v_add_f32_e32 v7, 1.0, v13
	v_add_f32_e32 v4, 1.0, v14
	v_add_f32_e32 v5, 1.0, v15
	v_rcp_f32_e32 v16, v6
	v_rcp_f32_e32 v17, v7
	v_rcp_f32_e32 v18, v4
	v_rcp_f32_e32 v19, v5
	v_med3_f32 v10, v10, s95, v182
	v_med3_f32 v11, v11, s95, v182
	v_mul_f32_e32 v10, s96, v10
	v_mul_f32_e32 v11, s96, v11
	v_mul_f32_e32 v8, s96, v8
	v_mul_f32_e32 v9, s96, v9
	v_fma_f32 v4, v144, v18, v26
	v_fma_f32 v5, v145, v19, v27
	v_fma_f32 v6, v142, v16, v24
	v_fma_f32 v7, v143, v17, v25
	v_mul_f32_e32 v12, v12, v16
	v_mul_f32_e32 v13, v13, v17
	v_mul_f32_e32 v14, v14, v18
	v_mul_f32_e32 v15, v15, v19
	v_exp_f32_e32 v16, v8
	v_exp_f32_e32 v17, v9
	v_exp_f32_e32 v18, v10
	v_exp_f32_e32 v19, v11
	v_log_f32_e32 v24, v6
	v_log_f32_e32 v25, v7
	v_log_f32_e32 v4, v4
	v_log_f32_e32 v5, v5
	v_add_f32_e32 v8, 1.0, v18
	v_add_f32_e32 v9, 1.0, v19
	v_add_f32_e32 v10, 1.0, v16
	v_add_f32_e32 v11, 1.0, v17
	v_rcp_f32_e32 v26, v8
	v_mul_f32_e32 v6, s68, v4
	v_mul_f32_e32 v7, s68, v5
	v_mul_f32_e32 v4, s68, v24
	v_mul_f32_e32 v5, s68, v25
	v_rcp_f32_e32 v24, v10
	v_rcp_f32_e32 v25, v11
	v_rcp_f32_e32 v27, v9
	v_mul_f32_e32 v14, v144, v14
	v_mul_f32_e32 v15, v145, v15
	v_mul_f32_e32 v12, v142, v12
	v_mul_f32_e32 v13, v143, v13
	v_fma_f32 v10, v2, v24, v20
	v_fma_f32 v11, v3, v25, v21
	v_fma_f32 v8, v140, v26, v22
	v_fma_f32 v9, v141, v27, v23
	v_log_f32_e32 v20, v10
	v_log_f32_e32 v21, v11
	v_log_f32_e32 v8, v8
	v_log_f32_e32 v9, v9
	v_mul_f32_e32 v16, v16, v24
	v_mul_f32_e32 v17, v17, v25
	v_cvt_pk_bf16_f32 v12, v12, v13
	v_cvt_pk_bf16_f32 v13, v14, v15
	v_mul_f32_e32 v10, s68, v8
	v_mul_f32_e32 v11, s68, v9
	v_mul_f32_e32 v2, v2, v16
	v_mul_f32_e32 v3, v3, v17
	v_mul_f32_e32 v8, s68, v20
	v_mul_f32_e32 v9, s68, v21
	v_cvt_pk_bf16_f32 v14, v2, v3
	v_lshl_add_u64 v[2:3], s[30:31], 0, v[0:1]
	v_add_co_u32_e32 v2, vcc, 0x4400000, v2
	v_mul_f32_e32 v18, v18, v26
	v_mul_f32_e32 v19, v19, v27
	s_nop 0
	v_addc_co_u32_e32 v3, vcc, 0, v3, vcc
	v_mul_f32_e32 v18, v140, v18
	v_mul_f32_e32 v19, v141, v19
	s_nop 0
	v_cvt_pk_bf16_f32 v15, v18, v19
	global_store_dwordx4 v[2:3], v[12:15], off

; #define LAS __attribute__((address_space(3)))
; __device__ __forceinline__ void mixer_hg2(const Args& a, Frame& F, bool ctx_out) {
;     ...
;             H2_STAGE(u);
;             MX_BAR();
;             { const int cn = (c + PF < NCH) ? c + PF : NCH - 1; H2_LOAD(cn, u); }
;             f32x4 fe, fu;
;             {
;                 unsigned one2_ = 0x3F803F80u; asm volatile("" : "+v"(one2_));
;                 typedef unsigned u4_ __attribute__((ext_vector_type(4)));
;                 const mx_bf16x8 ones = __builtin_bit_cast(mx_bf16x8, (u4_){one2_, one2_, one2_, one2_});
;                 const mx_bf16x8 a0 = frag_tr(L + 2 * IMG, QS, 0, 16 * w, lane), a1 = frag_tr(L + 2 * IMG, QS, 32, 16 * w, lane);
;                 const f32x4 z = ZERO4;
;                 f32x4 ct[4];
;                 ct[0] = MX_MFMA(a0, bt0, z); ct[1] = MX_MFMA(a0, bt1, z);
;                 const f32x4 cref = MX_MFMA(a0, ones, z);
;                 ct[2] = MX_MFMA(a1, bt0, cref); ct[3] = MX_MFMA(a1, bt1, cref);
;                 const f32x4 cend = MX_MFMA(a1, ones, cref);
;                 fe = (f32x4){__expf(cend[0]), __expf(cend[1]), __expf(cend[2]), __expf(cend[3])};
;                 fu = (f32x4){__expf(cend[0] - cref[0]), __expf(cend[1] - cref[1]), __expf(cend[2] - cref[2]), __expf(cend[3] - cref[3])};
;                 const f32x4 fs = {__expf(cref[0]), __expf(cref[1]), __expf(cref[2]), __expf(cref[3])};
; #pragma unroll
;                 for (int te = 0; te < 4; ++te) { const f32x4 s = accS[te] * fs; v2u sw; sw.x = pk2(s[0], s[1]); sw.y = pk2(s[2], s[3]);
;                     *(LAS v2u*)(L + O_ST + (16 * te + i) * QS + (16 * w + 4 * g) * 2) = sw; }
; #pragma unroll
;                 for (int t = 0; t < 4; ++t) {
;                     LAS unsigned char* pq = L + (16 * t + i) * QS + (16 * w + 4 * g) * 2;
;                     const v2u qw = *(const LAS v2u*)pq, kw = *(const LAS v2u*)(pq + IMG);
;                     const f32x4 dd = ct[t] - cref;
;                     const f32x4 tt = (f32x4){__builtin_amdgcn_fmed3f(dd[0], -80.f, 80.f), __builtin_amdgcn_fmed3f(dd[1], -80.f, 80.f), __builtin_amdgcn_fmed3f(dd[2], -80.f, 80.f), __builtin_amdgcn_fmed3f(dd[3], -80.f, 80.f)} * 1.4426950408889634f;
;                     const f32x4 e1 = {__builtin_amdgcn_exp2f(tt[0]), __builtin_amdgcn_exp2f(tt[1]), __builtin_amdgcn_exp2f(tt[2]), __builtin_amdgcn_exp2f(tt[3])};
.LBB0_510:
	s_waitcnt vmcnt(4)
	ds_write_b128 v251, v[94:97]
	s_waitcnt vmcnt(3)
	ds_write_b128 v251, v[98:101] offset:18432
	ds_write_b128 v251, v[102:105] offset:36864
	ds_write_b128 v250, v[110:113]
	s_waitcnt vmcnt(2)
	ds_write_b128 v250, v[106:109] offset:18432
	s_waitcnt vmcnt(1)
	ds_write_b128 v250, v[114:117] offset:36864
	s_waitcnt vmcnt(0)
	ds_write_b16 v249, v118 offset:55296
	ds_write_b16_d16_hi v249, v118 offset:55456
	ds_write_b16 v249, v119 offset:55616
	ds_write_b16_d16_hi v249, v119 offset:55776
	ds_write_b16 v249, v120 offset:55936
	ds_write_b16_d16_hi v249, v120 offset:56096
	ds_write_b16 v249, v121 offset:56256
	ds_write_b16_d16_hi v249, v121 offset:56416
	v_mov_b32_e32 v14, 0x3f803f80
	s_waitcnt lgkmcnt(0)
	s_barrier
	ds_read_b64_tr_b16 v[18:19], v245 offset:36864
	ds_read_b64_tr_b16 v[20:21], v245 offset:38016
	ds_read_b64_tr_b16 v[30:31], v245 offset:46080
	ds_read_b64_tr_b16 v[32:33], v245 offset:47232
	v_mov_b32_e32 v15, v14
	v_mov_b32_e32 v16, v14
	v_mov_b32_e32 v17, v14
	s_waitcnt lgkmcnt(2)
	v_mfma_f32_16x16x32_bf16 v[34:37], v[18:21], v[10:13], v[2:5]
	v_add_u32_e32 v54, v231, v232
	s_and_b64 s[24:25], s[24:25], exec
	s_cselect_b32 s24, 0xfc0, 0
	v_mfma_f32_16x16x32_bf16 v[14:17], v[18:21], v[14:17], v[2:5]
	s_or_b32 s7, s24, s7
	v_mfma_f32_16x16x32_bf16 v[26:29], v[18:21], v[6:9], v[2:5]
	s_waitcnt lgkmcnt(0)
	v_mfma_f32_16x16x32_bf16 v[22:25], v[30:33], v[10:13], v[14:17]
	s_nop 3
	v_mul_f32_e32 v18, 0x3fb8aa3b, v14
	v_mul_f32_e32 v19, 0x3fb8aa3b, v16
	v_exp_f32_e32 v38, v18
	v_mul_f32_e32 v18, 0x3fb8aa3b, v15
	v_exp_f32_e32 v40, v19
	v_mul_f32_e32 v19, 0x3fb8aa3b, v17
	v_exp_f32_e32 v41, v19
	v_exp_f32_e32 v39, v18
	v_mfma_f32_16x16x32_bf16 v[18:21], v[30:33], v[6:9], v[14:17]
	v_sub_f32_e32 v37, v37, v17
	v_mul_f32_e32 v30, v218, v40
	v_mul_f32_e32 v31, v219, v41
	v_mul_f32_e32 v32, v214, v38
	v_mul_f32_e32 v33, v215, v39
	v_sub_f32_e32 v36, v36, v16
	v_cvt_pk_bf16_f32 v32, v32, v33
	v_cvt_pk_bf16_f32 v33, v30, v31
	ds_write_b64 v246, v[32:33]
	v_mul_f32_e32 v30, v212, v40
	v_mul_f32_e32 v31, v213, v41
	v_mul_f32_e32 v32, v210, v38
	v_mul_f32_e32 v33, v211, v39
	v_sub_f32_e32 v35, v35, v15
	v_cvt_pk_bf16_f32 v32, v32, v33
	v_cvt_pk_bf16_f32 v33, v30, v31
	ds_write_b64 v246, v[32:33] offset:4608
	v_mul_f32_e32 v30, v208, v40
	v_mul_f32_e32 v31, v209, v41
	v_mul_f32_e32 v32, v206, v38
	v_mul_f32_e32 v33, v207, v39
	v_sub_f32_e32 v34, v34, v14
	v_cvt_pk_bf16_f32 v32, v32, v33
	v_cvt_pk_bf16_f32 v33, v30, v31
	v_med3_f32 v34, v34, s95, v182
	v_med3_f32 v35, v35, s95, v182
	v_med3_f32 v36, v36, s95, v182
	v_med3_f32 v37, v37, s95, v182
	ds_write_b64 v246, v[32:33] offset:9216
	v_mul_f32_e32 v30, v204, v40
	v_mul_f32_e32 v31, v205, v41
	v_mul_f32_e32 v32, v202, v38
	v_mul_f32_e32 v33, v203, v39
	v_mul_f32_e32 v36, s56, v36
	v_mul_f32_e32 v37, s56, v37
	v_mul_f32_e32 v34, s56, v34
	v_mul_f32_e32 v35, s56, v35
	v_cvt_pk_bf16_f32 v32, v32, v33
	v_cvt_pk_bf16_f32 v33, v30, v31
	v_exp_f32_e32 v34, v34
	v_exp_f32_e32 v35, v35
	v_exp_f32_e32 v36, v36
	v_exp_f32_e32 v37, v37
	ds_write_b64 v246, v[32:33] offset:13824
	ds_read_b64 v[30:31], v247
	ds_read_b64 v[32:33], v247 offset:18432
	v_sub_f32_e32 v29, v29, v17
	v_sub_f32_e32 v28, v28, v16
	v_sub_f32_e32 v27, v27, v15
	v_sub_f32_e32 v26, v26, v14
	v_rcp_f32_e32 v38, v34
	v_rcp_f32_e32 v39, v35
	v_rcp_f32_e32 v40, v36
	v_rcp_f32_e32 v41, v37
	v_med3_f32 v26, v26, s95, v182
	v_med3_f32 v27, v27, s95, v182
	v_med3_f32 v28, v28, s95, v182
	v_med3_f32 v29, v29, s95, v182
	v_mul_f32_e32 v28, s56, v28
	v_mul_f32_e32 v29, s56, v29
	v_mul_f32_e32 v26, s56, v26
	v_mul_f32_e32 v27, s56, v27
	v_exp_f32_e32 v28, v28
	v_exp_f32_e32 v26, v26
	v_exp_f32_e32 v27, v27
	v_exp_f32_e32 v29, v29
	s_waitcnt lgkmcnt(1)
	v_lshlrev_b32_e32 v48, 16, v30
	v_and_b32_e32 v49, 0xffff0000, v30
	v_lshlrev_b32_e32 v30, 16, v31
	v_and_b32_e32 v31, 0xffff0000, v31
	s_waitcnt lgkmcnt(0)
	v_lshlrev_b32_e32 v52, 16, v32
	v_and_b32_e32 v53, 0xffff0000, v32
	v_lshlrev_b32_e32 v32, 16, v33
	v_and_b32_e32 v33, 0xffff0000, v33
	v_mul_f32_e32 v30, v36, v30
	v_mul_f32_e32 v31, v37, v31
	v_mul_f32_e32 v34, v34, v48
	v_mul_f32_e32 v35, v35, v49
	v_mul_f32_e32 v32, v40, v32
	v_mul_f32_e32 v33, v41, v33
	v_mul_f32_e32 v38, v38, v52
	v_mul_f32_e32 v39, v39, v53
	ds_read_b64 v[42:43], v247 offset:4608
	ds_read_b64 v[44:45], v247 offset:9216
	ds_read_b64 v[46:47], v247 offset:13824
	v_cvt_pk_bf16_f32 v34, v34, v35
	v_cvt_pk_bf16_f32 v35, v30, v31
	v_cvt_pk_bf16_f32 v30, v38, v39
	v_cvt_pk_bf16_f32 v31, v32, v33
	v_sub_f32_e32 v25, v25, v17
	v_sub_f32_e32 v24, v24, v16
	v_sub_f32_e32 v23, v23, v15
	v_sub_f32_e32 v22, v22, v14
	ds_read_b64 v[36:37], v247 offset:23040
	ds_read_b64 v[48:49], v247 offset:27648
	ds_read_b64 v[50:51], v247 offset:32256
	ds_write_b64 v247, v[34:35]
	ds_write_b64 v247, v[30:31] offset:18432
	v_rcp_f32_e32 v30, v26
	v_rcp_f32_e32 v31, v27
	v_rcp_f32_e32 v32, v28
	v_rcp_f32_e32 v33, v29
	v_med3_f32 v22, v22, s95, v182
	v_med3_f32 v23, v23, s95, v182
	v_med3_f32 v24, v24, s95, v182
	v_med3_f32 v25, v25, s95, v182
	v_mul_f32_e32 v24, s56, v24
	v_mul_f32_e32 v25, s56, v25
	v_mul_f32_e32 v22, s56, v22
	v_mul_f32_e32 v23, s56, v23
	s_waitcnt lgkmcnt(7)
	v_lshlrev_b32_e32 v34, 16, v42
	v_and_b32_e32 v35, 0xffff0000, v42
	v_exp_f32_e32 v22, v22
	v_exp_f32_e32 v23, v23
	v_exp_f32_e32 v24, v24
	v_exp_f32_e32 v25, v25
	v_lshlrev_b32_e32 v38, 16, v43
	v_and_b32_e32 v39, 0xffff0000, v43
	v_mul_f32_e32 v26, v26, v34
	v_mul_f32_e32 v27, v27, v35
	s_waitcnt lgkmcnt(4)
; __device__ __forceinline__ void mixer_hg2(const Args& a, Frame& F, bool ctx_out) {
;     ...
; #pragma unroll
;                 for (int t = 0; t < 4; ++t) {
;                     LAS unsigned char* pq = L + (16 * t + i) * QS + (16 * w + 4 * g) * 2;
;                     const v2u qw = *(const LAS v2u*)pq, kw = *(const LAS v2u*)(pq + IMG);
;                     const f32x4 dd = ct[t] - cref;
;                     const f32x4 tt = (f32x4){__builtin_amdgcn_fmed3f(dd[0], -80.f, 80.f), __builtin_amdgcn_fmed3f(dd[1], -80.f, 80.f), __builtin_amdgcn_fmed3f(dd[2], -80.f, 80.f), __builtin_amdgcn_fmed3f(dd[3], -80.f, 80.f)} * 1.4426950408889634f;
;                     const f32x4 e1 = {__builtin_amdgcn_exp2f(tt[0]), __builtin_amdgcn_exp2f(tt[1]), __builtin_amdgcn_exp2f(tt[2]), __builtin_amdgcn_exp2f(tt[3])};
;                     const f32x4 e2 = {__builtin_amdgcn_rcpf(e1[0]), __builtin_amdgcn_rcpf(e1[1]), __builtin_amdgcn_rcpf(e1[2]), __builtin_amdgcn_rcpf(e1[3])};
;                     const f32x4 q4 = (f32x4){bflo(qw.x), bfhi(qw.x), bflo(qw.y), bfhi(qw.y)} * e1, k4 = (f32x4){bflo(kw.x), bfhi(kw.x), bflo(kw.y), bfhi(kw.y)} * e2;
;                     v2u qo, ko;
;                     qo.x = pk2(q4[0], q4[1]); qo.y = pk2(q4[2], q4[3]);
;                     ko.x = pk2(k4[0], k4[1]); ko.y = pk2(k4[2], k4[3]);
;                     *(LAS v2u*)pq = qo; *(LAS v2u*)(pq + IMG) = ko;
;                 }
;             }
;             MX_BAR();
;             const int rlo = H2_ROWLO(c);
;             const bool do_out = ctx_out || c >= NCTX;
;             mx_bf16x8 aq[KS];
;             {
;                 mx_bf16x8 kf[2][KS], vt[4][2];
;                 if (do_out) {
; #pragma unroll
;                     for (int ks = 0; ks < KS; ++ks) { aq[ks] = frag_row(L, QS, nq0, 32 * ks, lane); kf[0][ks] = frag_row(L + IMG, QS, 32 * cg, 32 * ks, lane); kf[1][ks] = frag_row(L + IMG, QS, 32 * cg + 16, 32 * ks, lane); }
;                 }
; #pragma unroll
;                 for (int te = 0; te < 4; ++te) { vt[te][0] = frag_row8(L + O_VT, 16 * te, 0, lane); vt[te][1] = frag_row8(L + O_VT, 16 * te, 32, lane); }
;                 const mx_bf16x8 ak0 = frag_tr(L + IMG, QS, 0, 16 * w, lane), ak1 = frag_tr(L + IMG, QS, 32, 16 * w, lane);
;                 __builtin_amdgcn_sched_barrier(0);
;                 f32x4 pt0 = ZERO4, pt1 = ZERO4;
;                 if (do_out) {
; #pragma unroll
	v_lshlrev_b32_e32 v34, 16, v36
	v_and_b32_e32 v35, 0xffff0000, v36
	v_lshlrev_b32_e32 v36, 16, v37
	v_and_b32_e32 v37, 0xffff0000, v37
	v_sub_f32_e32 v17, v21, v17
	v_sub_f32_e32 v16, v20, v16
	v_sub_f32_e32 v15, v19, v15
	v_sub_f32_e32 v14, v18, v14
	v_mul_f32_e32 v28, v28, v38
	v_mul_f32_e32 v29, v29, v39
	v_mul_f32_e32 v32, v32, v36
	v_mul_f32_e32 v33, v33, v37
	v_mul_f32_e32 v30, v30, v34
	v_mul_f32_e32 v31, v31, v35
	v_med3_f32 v14, v14, s95, v182
	v_med3_f32 v15, v15, s95, v182
	v_med3_f32 v16, v16, s95, v182
	v_med3_f32 v17, v17, s95, v182
	v_cvt_pk_bf16_f32 v26, v26, v27
	v_cvt_pk_bf16_f32 v27, v28, v29
	v_cvt_pk_bf16_f32 v28, v30, v31
	v_cvt_pk_bf16_f32 v29, v32, v33
	v_mul_f32_e32 v16, s56, v16
	v_mul_f32_e32 v17, s56, v17
	v_mul_f32_e32 v14, s56, v14
	v_mul_f32_e32 v15, s56, v15
	ds_write_b64 v247, v[26:27] offset:4608
	ds_write_b64 v247, v[28:29] offset:23040
	v_rcp_f32_e32 v26, v22
	v_rcp_f32_e32 v27, v23
	v_rcp_f32_e32 v28, v24
	v_rcp_f32_e32 v29, v25
	v_exp_f32_e32 v14, v14
	v_exp_f32_e32 v15, v15
	v_exp_f32_e32 v16, v16
	v_exp_f32_e32 v17, v17
	v_lshlrev_b32_e32 v30, 16, v44
	v_and_b32_e32 v31, 0xffff0000, v44
	v_lshlrev_b32_e32 v32, 16, v45
	v_and_b32_e32 v33, 0xffff0000, v45
	v_mul_f32_e32 v24, v24, v32
	v_mul_f32_e32 v25, v25, v33
	v_mul_f32_e32 v22, v22, v30
	v_mul_f32_e32 v23, v23, v31
	s_waitcnt lgkmcnt(5)
	v_lshlrev_b32_e32 v30, 16, v48
	v_and_b32_e32 v31, 0xffff0000, v48
	v_lshlrev_b32_e32 v32, 16, v49
	v_and_b32_e32 v33, 0xffff0000, v49
	v_mul_f32_e32 v28, v28, v32
	v_mul_f32_e32 v29, v29, v33
	v_mul_f32_e32 v26, v26, v30
	v_mul_f32_e32 v27, v27, v31
	v_rcp_f32_e32 v18, v14
	v_rcp_f32_e32 v19, v15
	v_rcp_f32_e32 v20, v16
	v_rcp_f32_e32 v21, v17
	v_cvt_pk_bf16_f32 v22, v22, v23
	v_cvt_pk_bf16_f32 v23, v24, v25
	v_cvt_pk_bf16_f32 v24, v26, v27
	v_cvt_pk_bf16_f32 v25, v28, v29
	ds_write_b64 v247, v[22:23] offset:9216
	ds_write_b64 v247, v[24:25] offset:27648
	v_lshlrev_b32_e32 v22, 16, v46
	v_and_b32_e32 v23, 0xffff0000, v46
	v_lshlrev_b32_e32 v24, 16, v47
	v_and_b32_e32 v25, 0xffff0000, v47
	v_mul_f32_e32 v16, v16, v24
	v_mul_f32_e32 v17, v17, v25
	v_mul_f32_e32 v14, v14, v22
	v_mul_f32_e32 v15, v15, v23
	s_waitcnt lgkmcnt(6)
	v_lshlrev_b32_e32 v22, 16, v50
	v_and_b32_e32 v23, 0xffff0000, v50
	v_lshlrev_b32_e32 v24, 16, v51
	v_and_b32_e32 v25, 0xffff0000, v51
	v_mul_f32_e32 v20, v20, v24
	v_mul_f32_e32 v21, v21, v25
	v_mul_f32_e32 v18, v18, v22
	v_mul_f32_e32 v19, v19, v23
	v_cvt_pk_bf16_f32 v14, v14, v15
	v_cvt_pk_bf16_f32 v15, v16, v17
	v_cvt_pk_bf16_f32 v16, v18, v19
	v_cvt_pk_bf16_f32 v17, v20, v21
	ds_write_b64 v247, v[14:15] offset:13824
	ds_write_b64 v247, v[16:17] offset:32256
	s_waitcnt lgkmcnt(0)
	s_barrier
	v_add_u32_e32 v42, v230, v232
	ds_read_b128 v[14:17], v42
	ds_read_b128 v[18:21], v42 offset:64
	ds_read_b128 v[30:33], v54 offset:18432
	ds_read_b128 v[38:41], v54 offset:18496
	ds_read_b128 v[26:29], v54 offset:23040
	ds_read_b128 v[34:37], v54 offset:23104
	ds_read_b128 v[22:25], v42 offset:128
	ds_read_b128 v[42:45], v42 offset:192
	ds_read_b128 v[50:53], v54 offset:18560
	ds_read_b128 v[58:61], v54 offset:18624
	ds_read_b128 v[46:49], v54 offset:23168
	ds_read_b128 v[54:57], v54 offset:23232
	s_waitcnt lgkmcnt(9)
	v_mfma_f32_16x16x32_bf16 v[62:65], v[30:33], v[14:17], v[2:5]
	s_waitcnt lgkmcnt(7)
	v_mfma_f32_16x16x32_bf16 v[66:69], v[26:29], v[14:17], v[2:5]
	v_mfma_f32_16x16x32_bf16 v[62:65], v[38:41], v[18:21], v[62:65]
	s_waitcnt lgkmcnt(6)
	v_mfma_f32_16x16x32_bf16 v[66:69], v[34:37], v[18:21], v[66:69]
	s_waitcnt lgkmcnt(3)
	v_mfma_f32_16x16x32_bf16 v[62:65], v[50:53], v[22:25], v[62:65]
	s_waitcnt lgkmcnt(1)
	v_mfma_f32_16x16x32_bf16 v[66:69], v[46:49], v[22:25], v[66:69]
	v_mfma_f32_16x16x32_bf16 v[62:65], v[58:61], v[42:45], v[62:65]
	s_waitcnt lgkmcnt(0)
	v_mfma_f32_16x16x32_bf16 v[66:69], v[54:57], v[42:45], v[66:69]
	s_nop 5
	v_cndmask_b32_e64 v62, v62, 0, s[8:9]
	v_cndmask_b32_e64 v63, 0, v63, s[10:11]
	v_cvt_pk_bf16_f32 v62, v62, v63
	v_cndmask_b32_e64 v63, v64, 0, s[12:13]
	v_cndmask_b32_e64 v64, v65, 0, s[14:15]
	v_cvt_pk_bf16_f32 v63, v63, v64
	v_add_u32_e32 v64, v233, v234
	ds_write_b64 v64, v[62:63]
	v_cndmask_b32_e64 v62, v66, 0, s[16:17]
	v_cndmask_b32_e64 v63, v67, 0, s[18:19]
	v_cvt_pk_bf16_f32 v62, v62, v63
	v_cndmask_b32_e64 v63, v68, 0, s[20:21]
	v_cndmask_b32_e64 v64, v69, 0, s[22:23]
	v_cvt_pk_bf16_f32 v63, v63, v64
	v_add_u32_e32 v64, v233, v235
	ds_write_b64 v64, v[62:63]
	v_add_u32_e32 v90, v242, v232
	ds_read_b128 v[62:65], v90
	ds_read_b128 v[66:69], v90 offset:64
	ds_read_b128 v[70:73], v90 offset:128
	ds_read_b128 v[74:77], v90 offset:192
	ds_read_b128 v[78:81], v90 offset:4608
	ds_read_b128 v[82:85], v90 offset:4672
	ds_read_b128 v[86:89], v90 offset:4736
	ds_read_b128 v[90:93], v90 offset:4800
	s_waitcnt lgkmcnt(0)
	s_barrier
	v_add_u32_e32 v98, v233, v232
	v_add_u32_e32 v114, v243, v232
	ds_read_b128 v[94:97], v98
	ds_read_b128 v[98:101], v98 offset:64
	ds_read_b128 v[102:105], v114 offset:55296
	ds_read_b128 v[106:109], v114 offset:55360
	ds_read_b128 v[110:113], v114 offset:57856
	ds_read_b128 v[114:117], v114 offset:57920
	s_waitcnt lgkmcnt(3)
	v_mfma_f32_16x16x32_bf16 v[102:105], v[102:105], v[94:97], v[2:5]
	s_add_i32 s6, s6, s3
	s_cmpk_gt_i32 s6, 0xff
	s_waitcnt lgkmcnt(1)
	v_mfma_f32_16x16x32_bf16 v[94:97], v[110:113], v[94:97], v[2:5]
	v_add_u32_e32 v110, s7, v248
	v_ashrrev_i32_e32 v111, 31, v110
	v_lshlrev_b64 v[110:111], 12, v[110:111]
	v_mfma_f32_16x16x32_bf16 v[102:105], v[62:65], v[14:17], v[102:105]
	v_mfma_f32_16x16x32_bf16 v[94:97], v[78:81], v[14:17], v[94:97]
	v_mfma_f32_16x16x32_bf16 v[102:105], v[66:69], v[18:21], v[102:105]
	v_mfma_f32_16x16x32_bf16 v[94:97], v[82:85], v[18:21], v[94:97]
	v_mfma_f32_16x16x32_bf16 v[102:105], v[70:73], v[22:25], v[102:105]
	v_mfma_f32_16x16x32_bf16 v[94:97], v[86:89], v[22:25], v[94:97]
	v_mfma_f32_16x16x32_bf16 v[102:105], v[74:77], v[42:45], v[102:105]
	v_mfma_f32_16x16x32_bf16 v[94:97], v[90:93], v[42:45], v[94:97]
	v_mfma_f32_16x16x32_bf16 v[102:105], v[106:109], v[98:101], v[102:105]
	v_lshl_add_u64 v[106:107], v[194:195], 0, v[110:111]
	s_waitcnt lgkmcnt(0)
	v_mfma_f32_16x16x32_bf16 v[94:97], v[114:117], v[98:101], v[94:97]
	s_nop 4
	v_cvt_pk_bf16_f32 v102, v102, v103
	v_cvt_pk_bf16_f32 v103, v104, v105
	s_nop 0
	v_cvt_pk_bf16_f32 v94, v94, v95
	v_cvt_pk_bf16_f32 v95, v96, v97
	global_store_dwordx2 v[106:107], v[102:103], off
	global_store_dwordx2 v[106:107], v[94:95], off offset:32
	s_waitcnt lgkmcnt(0)
	s_barrier
	s_cbranch_scc1 .LBB0_524

; __device__ __forceinline__ void mixer_hg2(const Args& a, Frame& F, bool ctx_out) {
;     ...
;         __syncthreads();
; #pragma unroll
;         for (int u = 0; u < PF; ++u) H2_LOAD(u, u);
;         for (int c0 = 0; c0 < NCH; c0 += PF)
; #pragma unroll
;         for (int u = 0; u < PF; ++u) {
;             const int c = c0 + u;
;             H2_STAGE(u);
;             MX_BAR();
;             { const int cn = (c + PF < NCH) ? c + PF : NCH - 1; H2_LOAD(cn, u); }
;             f32x4 fe, fu;
;             {
;                 unsigned one2_ = 0x3F803F80u; asm volatile("" : "+v"(one2_));
;                 typedef unsigned u4_ __attribute__((ext_vector_type(4)));
;                 const mx_bf16x8 ones = __builtin_bit_cast(mx_bf16x8, (u4_){one2_, one2_, one2_, one2_});
;                 const mx_bf16x8 a0 = frag_tr(L + 2 * IMG, QS, 0, 16 * w, lane), a1 = frag_tr(L + 2 * IMG, QS, 32, 16 * w, lane);
;                 const f32x4 z = ZERO4;
;                 f32x4 ct[4];
;                 ct[0] = MX_MFMA(a0, bt0, z); ct[1] = MX_MFMA(a0, bt1, z);
;                 const f32x4 cref = MX_MFMA(a0, ones, z);
;                 ct[2] = MX_MFMA(a1, bt0, cref); ct[3] = MX_MFMA(a1, bt1, cref);
;                 const f32x4 cend = MX_MFMA(a1, ones, cref);
;                 fe = (f32x4){__expf(cend[0]), __expf(cend[1]), __expf(cend[2]), __expf(cend[3])};
;                 fu = (f32x4){__expf(cend[0] - cref[0]), __expf(cend[1] - cref[1]), __expf(cend[2] - cref[2]), __expf(cend[3] - cref[3])};
;                 const f32x4 fs = {__expf(cref[0]), __expf(cref[1]), __expf(cref[2]), __expf(cref[3])};
; #pragma unroll
;                 for (int te = 0; te < 4; ++te) { const f32x4 s = accS[te] * fs; v2u sw; sw.x = pk2(s[0], s[1]); sw.y = pk2(s[2], s[3]);
;                     *(LAS v2u*)(L + O_ST + (16 * te + i) * QS + (16 * w + 4 * g) * 2) = sw; }
; #pragma unroll
;                 for (int t = 0; t < 4; ++t) {
;                     LAS unsigned char* pq = L + (16 * t + i) * QS + (16 * w + 4 * g) * 2;
;                     const v2u qw = *(const LAS v2u*)pq, kw = *(const LAS v2u*)(pq + IMG);
;                     const f32x4 dd = ct[t] - cref;
;                     const f32x4 tt = (f32x4){__builtin_amdgcn_fmed3f(dd[0], -80.f, 80.f), __builtin_amdgcn_fmed3f(dd[1], -80.f, 80.f), __builtin_amdgcn_fmed3f(dd[2], -80.f, 80.f), __builtin_amdgcn_fmed3f(dd[3], -80.f, 80.f)} * 1.4426950408889634f;
.LBB0_512:
	s_add_i32 s29, s31, 1
	s_add_i32 s36, s30, -1
	v_sub_co_u32_e64 v122, s[34:35], s31, 3
	s_and_b64 s[26:27], s[24:25], exec
	v_readfirstlane_b32 s26, v122
	s_cselect_b32 s26, s26, s36
	s_lshl_b32 s37, s26, 6
	s_add_i32 s40, s30, 0xffffffbf
	s_and_b64 s[26:27], s[24:25], exec
	s_cselect_b32 s26, s29, s40
	s_lshl_b32 s26, s26, 6
	s_add_i32 s40, s26, s33
	s_cmp_gt_u32 s31, 3
	s_cselect_b64 s[26:27], -1, 0
	s_add_i32 s37, s37, s7
	s_and_b64 s[34:35], s[34:35], exec
	s_cselect_b32 s34, s40, s37
	s_waitcnt vmcnt(4)
	ds_write_b128 v251, v[94:97]
	s_waitcnt vmcnt(3)
	ds_write_b128 v251, v[98:101] offset:18432
	ds_write_b128 v251, v[102:105] offset:36864
	ds_write_b128 v250, v[110:113]
	s_waitcnt vmcnt(2)
	ds_write_b128 v250, v[106:109] offset:18432
	s_waitcnt vmcnt(1)
	ds_write_b128 v250, v[114:117] offset:36864
	s_waitcnt vmcnt(0)
	ds_write_b16 v249, v118 offset:55296
	ds_write_b16_d16_hi v249, v118 offset:55456
	ds_write_b16 v249, v119 offset:55616
	ds_write_b16_d16_hi v249, v119 offset:55776
	ds_write_b16 v249, v120 offset:55936
	ds_write_b16_d16_hi v249, v120 offset:56096
	ds_write_b16 v249, v121 offset:56256
	ds_write_b16_d16_hi v249, v121 offset:56416
	v_add_u32_e32 v94, s34, v237
	v_add_u32_e32 v106, s34, v238
	v_ashrrev_i32_e32 v95, 31, v94
	v_ashrrev_i32_e32 v107, 31, v106
	v_lshlrev_b64 v[94:95], 11, v[94:95]
	v_lshlrev_b64 v[106:107], 11, v[106:107]
	v_lshl_add_u64 v[94:95], v[94:95], 0, v[200:201]
	v_lshl_add_u64 v[106:107], v[106:107], 0, v[200:201]
	v_or_b32_e32 v118, s34, v185
	v_lshlrev_b64 v[102:103], 1, v[94:95]
	v_lshlrev_b64 v[114:115], 1, v[106:107]
	v_ashrrev_i32_e32 v119, 31, v118
	s_waitcnt lgkmcnt(0)
	s_barrier
	v_lshl_add_u64 v[94:95], v[188:189], 0, v[102:103]
	v_lshl_add_u64 v[98:99], v[196:197], 0, v[102:103]
	v_lshl_add_u64 v[102:103], v[198:199], 0, v[102:103]
	v_lshl_add_u64 v[106:107], v[188:189], 0, v[114:115]
	v_lshlrev_b64 v[118:119], 12, v[118:119]
	global_load_dwordx4 v[102:105], v[102:103], off
	v_lshl_add_u64 v[118:119], v[216:217], 0, v[118:119]
	global_load_dwordx4 v[110:113], v[106:107], off
	v_lshl_add_u64 v[106:107], v[196:197], 0, v[114:115]
	v_lshl_add_u64 v[114:115], v[198:199], 0, v[114:115]
	global_load_dwordx4 v[94:97], v[94:95], off
	v_mov_b32_e32 v126, 0x3f803f80
	global_load_dwordx4 v[98:101], v[98:99], off
	s_or_b64 s[34:35], s[4:5], s[26:27]
	global_load_dwordx4 v[106:109], v[106:107], off
	s_and_b64 vcc, exec, s[34:35]
	global_load_dwordx4 v[114:117], v[114:115], off
	s_nop 0
	global_load_dwordx4 v[118:121], v[118:119], off
	ds_read_b64_tr_b16 v[122:123], v245 offset:36864
	ds_read_b64_tr_b16 v[124:125], v245 offset:38016
	ds_read_b64_tr_b16 v[138:139], v245 offset:46080
	ds_read_b64_tr_b16 v[140:141], v245 offset:47232
	v_mov_b32_e32 v127, v126
	v_mov_b32_e32 v128, v126
	v_mov_b32_e32 v129, v126
	s_waitcnt lgkmcnt(2)
	v_mfma_f32_16x16x32_bf16 v[142:145], v[122:125], v[10:13], v[2:5]
	v_mfma_f32_16x16x32_bf16 v[146:149], v[122:125], v[6:9], v[2:5]
	v_mfma_f32_16x16x32_bf16 v[122:125], v[122:125], v[126:129], v[2:5]
	s_waitcnt lgkmcnt(0)
	v_mfma_f32_16x16x32_bf16 v[134:137], v[138:141], v[10:13], v[122:125]
	v_mfma_f32_16x16x32_bf16 v[130:133], v[138:141], v[6:9], v[122:125]
	s_nop 4
	v_sub_f32_e32 v145, v145, v125
	v_sub_f32_e32 v144, v144, v124
	v_sub_f32_e32 v143, v143, v123
	v_mfma_f32_16x16x32_bf16 v[126:129], v[138:141], v[126:129], v[122:125]
	v_mul_f32_e32 v138, 0x3fb8aa3b, v122
	v_mul_f32_e32 v139, 0x3fb8aa3b, v123
	v_mul_f32_e32 v140, 0x3fb8aa3b, v124
	v_mul_f32_e32 v141, 0x3fb8aa3b, v125
	v_exp_f32_e32 v138, v138
	v_exp_f32_e32 v139, v139
	v_exp_f32_e32 v140, v140
	v_exp_f32_e32 v141, v141
	v_sub_f32_e32 v142, v142, v122
	v_mul_f32_e32 v152, v214, v138
	v_mul_f32_e32 v153, v215, v139
	v_med3_f32 v142, v142, s95, v182
	v_mul_f32_e32 v150, v218, v140
	v_mul_f32_e32 v151, v219, v141
	v_cvt_pk_bf16_f32 v152, v152, v153
	v_cvt_pk_bf16_f32 v153, v150, v151
	ds_write_b64 v246, v[152:153]
	v_mul_f32_e32 v150, v212, v140
	v_mul_f32_e32 v151, v213, v141
	v_mul_f32_e32 v152, v210, v138
	v_mul_f32_e32 v153, v211, v139
	v_med3_f32 v143, v143, s95, v182
	v_cvt_pk_bf16_f32 v152, v152, v153
	v_cvt_pk_bf16_f32 v153, v150, v151
	v_med3_f32 v144, v144, s95, v182
	v_med3_f32 v145, v145, s95, v182
	ds_write_b64 v246, v[152:153] offset:4608
	v_mul_f32_e32 v150, v208, v140
	v_mul_f32_e32 v151, v209, v141
	v_mul_f32_e32 v152, v206, v138
	v_mul_f32_e32 v153, v207, v139
	v_mul_f32_e32 v140, v204, v140
	v_mul_f32_e32 v141, v205, v141
	v_mul_f32_e32 v138, v202, v138
	v_mul_f32_e32 v139, v203, v139
	v_mul_f32_e32 v144, s56, v144
	v_mul_f32_e32 v145, s56, v145
	v_mul_f32_e32 v142, s56, v142
	v_mul_f32_e32 v143, s56, v143
	v_cvt_pk_bf16_f32 v152, v152, v153
	v_cvt_pk_bf16_f32 v153, v150, v151
	v_cvt_pk_bf16_f32 v138, v138, v139
	v_cvt_pk_bf16_f32 v139, v140, v141
	v_exp_f32_e32 v142, v142
	v_exp_f32_e32 v143, v143
	v_exp_f32_e32 v144, v144
	v_exp_f32_e32 v145, v145
	ds_write_b64 v246, v[152:153] offset:9216
	ds_write_b64 v246, v[138:139] offset:13824
	ds_read_b64 v[138:139], v247
	ds_read_b64 v[140:141], v247 offset:18432
	v_rcp_f32_e32 v150, v142
	v_rcp_f32_e32 v151, v143
	v_rcp_f32_e32 v152, v144
	v_rcp_f32_e32 v153, v145
	s_waitcnt lgkmcnt(1)
	v_lshlrev_b32_e32 v154, 16, v138
	v_and_b32_e32 v155, 0xffff0000, v138
	v_lshlrev_b32_e32 v138, 16, v139
	v_and_b32_e32 v139, 0xffff0000, v139
	v_mul_f32_e32 v138, v144, v138
	v_mul_f32_e32 v139, v145, v139
	v_mul_f32_e32 v142, v142, v154
	v_mul_f32_e32 v143, v143, v155
	s_waitcnt lgkmcnt(0)
; #define LAS __attribute__((address_space(3)))
; __device__ __forceinline__ unsigned pk2(float lo, float hi) { const f32x2_t v = {lo, hi}; const bf16x2_t b = __builtin_convertvector(v, bf16x2_t); return __builtin_bit_cast(unsigned, b); }
; #define MX_BAR() do { asm volatile("s_waitcnt lgkmcnt(0)" ::: "memory"); __builtin_amdgcn_s_barrier(); if (MXP_BAR > 1) __builtin_amdgcn_s_barrier(); asm volatile("" ::: "memory"); } while (0)
; __device__ __forceinline__ void mixer_hg2(const Args& a, Frame& F, bool ctx_out) {
;     ...
; #pragma unroll
;                 for (int t = 0; t < 4; ++t) {
;                     LAS unsigned char* pq = L + (16 * t + i) * QS + (16 * w + 4 * g) * 2;
;                     const v2u qw = *(const LAS v2u*)pq, kw = *(const LAS v2u*)(pq + IMG);
;                     const f32x4 dd = ct[t] - cref;
;                     const f32x4 tt = (f32x4){__builtin_amdgcn_fmed3f(dd[0], -80.f, 80.f), __builtin_amdgcn_fmed3f(dd[1], -80.f, 80.f), __builtin_amdgcn_fmed3f(dd[2], -80.f, 80.f), __builtin_amdgcn_fmed3f(dd[3], -80.f, 80.f)} * 1.4426950408889634f;
;                     const f32x4 e1 = {__builtin_amdgcn_exp2f(tt[0]), __builtin_amdgcn_exp2f(tt[1]), __builtin_amdgcn_exp2f(tt[2]), __builtin_amdgcn_exp2f(tt[3])};
;                     const f32x4 e2 = {__builtin_amdgcn_rcpf(e1[0]), __builtin_amdgcn_rcpf(e1[1]), __builtin_amdgcn_rcpf(e1[2]), __builtin_amdgcn_rcpf(e1[3])};
;                     const f32x4 q4 = (f32x4){bflo(qw.x), bfhi(qw.x), bflo(qw.y), bfhi(qw.y)} * e1, k4 = (f32x4){bflo(kw.x), bfhi(kw.x), bflo(kw.y), bfhi(kw.y)} * e2;
;                     v2u qo, ko;
;                     qo.x = pk2(q4[0], q4[1]); qo.y = pk2(q4[2], q4[3]);
;                     ko.x = pk2(k4[0], k4[1]); ko.y = pk2(k4[2], k4[3]);
;                     *(LAS v2u*)pq = qo; *(LAS v2u*)(pq + IMG) = ko;
;                 }
;             }
;             MX_BAR();
;             const int rlo = H2_ROWLO(c);
;             const bool do_out = ctx_out || c >= NCTX;
;             mx_bf16x8 aq[KS];
;             {
;                 mx_bf16x8 kf[2][KS], vt[4][2];
;                 if (do_out) {
; #pragma unroll
;                     for (int ks = 0; ks < KS; ++ks) { aq[ks] = frag_row(L, QS, nq0, 32 * ks, lane); kf[0][ks] = frag_row(L + IMG, QS, 32 * cg, 32 * ks, lane); kf[1][ks] = frag_row(L + IMG, QS, 32 * cg + 16, 32 * ks, lane); }
	v_lshlrev_b32_e32 v144, 16, v140
	v_and_b32_e32 v145, 0xffff0000, v140
	v_lshlrev_b32_e32 v140, 16, v141
	v_and_b32_e32 v141, 0xffff0000, v141
	v_mul_f32_e32 v140, v152, v140
	v_mul_f32_e32 v141, v153, v141
	v_mul_f32_e32 v144, v150, v144
	v_mul_f32_e32 v145, v151, v145
	v_cvt_pk_bf16_f32 v142, v142, v143
	v_cvt_pk_bf16_f32 v143, v138, v139
	v_cvt_pk_bf16_f32 v138, v144, v145
	v_cvt_pk_bf16_f32 v139, v140, v141
	ds_write_b64 v247, v[142:143]
	ds_write_b64 v247, v[138:139] offset:18432
	v_sub_f32_e32 v145, v149, v125
	v_sub_f32_e32 v144, v148, v124
	v_sub_f32_e32 v143, v147, v123
	v_sub_f32_e32 v142, v146, v122
	v_med3_f32 v142, v142, s95, v182
	v_med3_f32 v143, v143, s95, v182
	v_med3_f32 v144, v144, s95, v182
	v_med3_f32 v145, v145, s95, v182
	v_mul_f32_e32 v144, s56, v144
	v_mul_f32_e32 v145, s56, v145
	v_mul_f32_e32 v142, s56, v142
	v_mul_f32_e32 v143, s56, v143
	v_exp_f32_e32 v144, v144
	v_exp_f32_e32 v142, v142
	v_exp_f32_e32 v143, v143
	v_exp_f32_e32 v145, v145
	ds_read_b64 v[138:139], v247 offset:4608
	ds_read_b64 v[140:141], v247 offset:23040
	v_rcp_f32_e32 v146, v142
	v_rcp_f32_e32 v147, v143
	v_rcp_f32_e32 v148, v144
	v_rcp_f32_e32 v149, v145
	v_sub_f32_e32 v137, v137, v125
	v_sub_f32_e32 v136, v136, v124
	v_sub_f32_e32 v135, v135, v123
	v_sub_f32_e32 v134, v134, v122
	s_waitcnt lgkmcnt(1)
	v_lshlrev_b32_e32 v150, 16, v138
	v_and_b32_e32 v151, 0xffff0000, v138
	v_lshlrev_b32_e32 v138, 16, v139
	v_and_b32_e32 v139, 0xffff0000, v139
	v_med3_f32 v134, v134, s95, v182
	v_med3_f32 v135, v135, s95, v182
	v_med3_f32 v136, v136, s95, v182
	v_med3_f32 v137, v137, s95, v182
	v_mul_f32_e32 v138, v144, v138
	v_mul_f32_e32 v139, v145, v139
	v_mul_f32_e32 v142, v142, v150
	v_mul_f32_e32 v143, v143, v151
	s_waitcnt lgkmcnt(0)
	v_lshlrev_b32_e32 v144, 16, v140
	v_and_b32_e32 v145, 0xffff0000, v140
	v_lshlrev_b32_e32 v140, 16, v141
	v_and_b32_e32 v141, 0xffff0000, v141
	v_mul_f32_e32 v136, s56, v136
	v_mul_f32_e32 v137, s56, v137
	v_mul_f32_e32 v134, s56, v134
	v_mul_f32_e32 v135, s56, v135
	v_mul_f32_e32 v140, v148, v140
	v_mul_f32_e32 v141, v149, v141
	v_mul_f32_e32 v144, v146, v144
	v_mul_f32_e32 v145, v147, v145
	v_cvt_pk_bf16_f32 v142, v142, v143
	v_cvt_pk_bf16_f32 v143, v138, v139
	v_exp_f32_e32 v134, v134
	v_exp_f32_e32 v135, v135
	v_exp_f32_e32 v136, v136
	v_exp_f32_e32 v137, v137
	v_cvt_pk_bf16_f32 v138, v144, v145
	v_cvt_pk_bf16_f32 v139, v140, v141
	ds_write_b64 v247, v[142:143] offset:4608
	ds_write_b64 v247, v[138:139] offset:23040
	ds_read_b64 v[138:139], v247 offset:9216
	ds_read_b64 v[140:141], v247 offset:27648
	v_rcp_f32_e32 v142, v134
	v_rcp_f32_e32 v143, v135
	v_rcp_f32_e32 v144, v136
	v_rcp_f32_e32 v145, v137
	v_sub_f32_e32 v133, v133, v125
	v_sub_f32_e32 v132, v132, v124
	v_sub_f32_e32 v131, v131, v123
	v_sub_f32_e32 v130, v130, v122
	s_waitcnt lgkmcnt(1)
	v_lshlrev_b32_e32 v146, 16, v138
	v_and_b32_e32 v147, 0xffff0000, v138
	v_lshlrev_b32_e32 v138, 16, v139
	v_and_b32_e32 v139, 0xffff0000, v139
	v_med3_f32 v130, v130, s95, v182
	v_med3_f32 v131, v131, s95, v182
	v_med3_f32 v132, v132, s95, v182
	v_med3_f32 v133, v133, s95, v182
	v_mul_f32_e32 v136, v136, v138
	v_mul_f32_e32 v137, v137, v139
	v_mul_f32_e32 v134, v134, v146
	v_mul_f32_e32 v135, v135, v147
	s_waitcnt lgkmcnt(0)
	v_lshlrev_b32_e32 v138, 16, v140
	v_and_b32_e32 v139, 0xffff0000, v140
	v_lshlrev_b32_e32 v140, 16, v141
	v_and_b32_e32 v141, 0xffff0000, v141
	v_mul_f32_e32 v132, s56, v132
	v_mul_f32_e32 v133, s56, v133
	v_mul_f32_e32 v130, s56, v130
	v_mul_f32_e32 v131, s56, v131
	v_mul_f32_e32 v140, v144, v140
	v_mul_f32_e32 v141, v145, v141
	v_mul_f32_e32 v138, v142, v138
	v_mul_f32_e32 v139, v143, v139
	v_cvt_pk_bf16_f32 v134, v134, v135
	v_cvt_pk_bf16_f32 v135, v136, v137
	v_exp_f32_e32 v130, v130
	v_exp_f32_e32 v131, v131
	v_exp_f32_e32 v132, v132
	v_exp_f32_e32 v133, v133
	v_cvt_pk_bf16_f32 v136, v138, v139
	v_cvt_pk_bf16_f32 v137, v140, v141
	ds_write_b64 v247, v[134:135] offset:9216
	ds_write_b64 v247, v[136:137] offset:27648
	ds_read_b64 v[134:135], v247 offset:13824
	ds_read_b64 v[136:137], v247 offset:32256
	v_rcp_f32_e32 v138, v130
	v_rcp_f32_e32 v139, v131
	v_rcp_f32_e32 v140, v132
	v_rcp_f32_e32 v141, v133
	s_waitcnt lgkmcnt(1)
	v_lshlrev_b32_e32 v142, 16, v134
	v_and_b32_e32 v143, 0xffff0000, v134
	v_lshlrev_b32_e32 v134, 16, v135
	v_and_b32_e32 v135, 0xffff0000, v135
	v_mul_f32_e32 v132, v132, v134
	v_mul_f32_e32 v133, v133, v135
	v_mul_f32_e32 v130, v130, v142
	v_mul_f32_e32 v131, v131, v143
	s_waitcnt lgkmcnt(0)
	v_lshlrev_b32_e32 v134, 16, v136
	v_and_b32_e32 v135, 0xffff0000, v136
	v_lshlrev_b32_e32 v136, 16, v137
	v_and_b32_e32 v137, 0xffff0000, v137
	v_mul_f32_e32 v136, v140, v136
	v_mul_f32_e32 v137, v141, v137
	v_mul_f32_e32 v134, v138, v134
	v_mul_f32_e32 v135, v139, v135
	v_cvt_pk_bf16_f32 v130, v130, v131
	v_cvt_pk_bf16_f32 v131, v132, v133
	v_cvt_pk_bf16_f32 v132, v134, v135
	v_cvt_pk_bf16_f32 v133, v136, v137
	ds_write_b64 v247, v[130:131] offset:13824
	ds_write_b64 v247, v[132:133] offset:32256
	s_waitcnt lgkmcnt(0)
	s_barrier
	s_cbranch_vccz .LBB0_514
	v_add_u32_e32 v42, v230, v232
	v_add_u32_e32 v54, v231, v232
	ds_read_b128 v[14:17], v42
	ds_read_b128 v[18:21], v42 offset:64
	ds_read_b128 v[30:33], v54 offset:18432
	ds_read_b128 v[38:41], v54 offset:18496
	ds_read_b128 v[26:29], v54 offset:23040
	ds_read_b128 v[34:37], v54 offset:23104
	ds_read_b128 v[22:25], v42 offset:128
	ds_read_b128 v[42:45], v42 offset:192
	ds_read_b128 v[50:53], v54 offset:18560
	ds_read_b128 v[58:61], v54 offset:18624
	ds_read_b128 v[46:49], v54 offset:23168
	ds_read_b128 v[54:57], v54 offset:23232

; __device__ __forceinline__ void mixer_hg2(const Args& a, Frame& F, bool ctx_out) {
;     ...
;                 fe = (f32x4){__expf(cend[0]), __expf(cend[1]), __expf(cend[2]), __expf(cend[3])};
;                 fu = (f32x4){__expf(cend[0] - cref[0]), __expf(cend[1] - cref[1]), __expf(cend[2] - cref[2]), __expf(cend[3] - cref[3])};
;     ...
;                 for (int te = 0; te < 4; ++te) accS[te] = accS[te] * fe + uu[te] * fu;
.LBB0_522:
	v_sub_f32_e32 v122, v126, v122
	v_sub_f32_e32 v123, v127, v123
	v_sub_f32_e32 v124, v128, v124
	v_sub_f32_e32 v125, v129, v125
	v_mul_f32_e32 v122, 0x3fb8aa3b, v122
	v_mul_f32_e32 v123, 0x3fb8aa3b, v123
	v_mul_f32_e32 v124, 0x3fb8aa3b, v124
	v_mul_f32_e32 v125, 0x3fb8aa3b, v125
	v_mul_f32_e32 v146, 0x3fb8aa3b, v126
	v_mul_f32_e32 v147, 0x3fb8aa3b, v127
	v_mul_f32_e32 v148, 0x3fb8aa3b, v128
	v_mul_f32_e32 v149, 0x3fb8aa3b, v129
	v_exp_f32_e32 v122, v122
	v_exp_f32_e32 v123, v123
	v_exp_f32_e32 v124, v124
	v_exp_f32_e32 v125, v125
	v_exp_f32_e32 v146, v146
	v_exp_f32_e32 v148, v148
	v_exp_f32_e32 v149, v149
	v_exp_f32_e32 v147, v147
	v_mul_f32_e32 v126, v122, v142
	v_mul_f32_e32 v127, v123, v143
	v_mul_f32_e32 v128, v124, v144
	v_mul_f32_e32 v129, v125, v145
	s_waitcnt lgkmcnt(0)
	v_fma_f32 v214, v214, v146, v126
	v_fma_f32 v215, v215, v147, v127
	v_fma_f32 v218, v218, v148, v128
	v_fma_f32 v219, v219, v149, v129
	v_mul_f32_e32 v126, v122, v138
	v_mul_f32_e32 v127, v123, v139
	v_mul_f32_e32 v128, v124, v140
	v_mul_f32_e32 v129, v125, v141
	s_barrier
	v_fma_f32 v212, v212, v148, v128
	v_fma_f32 v213, v213, v149, v129
	v_fma_f32 v210, v210, v146, v126
	v_fma_f32 v211, v211, v147, v127
	v_mul_f32_e32 v126, v122, v134
	v_mul_f32_e32 v127, v123, v135
	v_mul_f32_e32 v128, v124, v136
	v_mul_f32_e32 v129, v125, v137
	v_mul_f32_e32 v122, v122, v130
	v_mul_f32_e32 v123, v123, v131
	v_mul_f32_e32 v124, v124, v132
	v_mul_f32_e32 v125, v125, v133
	v_fma_f32 v208, v208, v148, v128
	v_fma_f32 v209, v209, v149, v129
	v_fma_f32 v206, v206, v146, v126
	v_fma_f32 v207, v207, v147, v127
	v_fma_f32 v204, v204, v148, v124
	v_fma_f32 v205, v205, v149, v125
	v_fma_f32 v202, v202, v146, v122
	v_fma_f32 v203, v203, v147, v123
	s_cmpk_eq_i32 s29, 0x43
	s_cbranch_scc1 .LBB0_510
	s_mov_b32 s30, s36
	s_mov_b32 s31, s29
	s_branch .LBB0_512

; #define GAS __attribute__((address_space(1)))
; __device__ __forceinline__ unsigned pk2(float lo, float hi) { const f32x2_t v = {lo, hi}; const bf16x2_t b = __builtin_convertvector(v, bf16x2_t); return __builtin_bit_cast(unsigned, b); }
; template <bool HG>
; __device__ __forceinline__ void readout_phase(const Args& a, Frame& F, const float* gain, int nrows) {
;     ...
;     for (int r = gw; r < nrows; r += NGW) {
;         const GAS v2u* f = (const GAS v2u*)(OF + (size_t)r * D) + F.lane; const GAS v2u* bk = (const GAS v2u*)(OB + (size_t)r * D) + F.lane;
;         const GAS v2u* g8 = (const GAS v2u*)(G + (size_t)r * D) + F.lane;
;         f32x4 v[8]; float ssj[8]; float tot = 0.f;
; #pragma unroll
;         for (int j = 0; j < 8; ++j) { const v2u fa = EW_NT ? __builtin_nontemporal_load(f + 64 * j) : f[64 * j], fb = EW_NT ? __builtin_nontemporal_load(bk + 64 * j) : bk[64 * j]; v[j] = (f32x4){bflo(fa.x) + bflo(fb.x), bfhi(fa.x) + bfhi(fb.x), bflo(fa.y) + bflo(fb.y), bfhi(fa.y) + bfhi(fb.y)}; ssj[j] = (v[j][0] * v[j][0] + v[j][1] * v[j][1]) + (v[j][2] * v[j][2] + v[j][3] * v[j][3]); tot += ssj[j]; }
;         float rs_all = 0.f;
;         if (HG) rs_all = 1.0f / sqrtf(wave_sum(tot) * (1.0f / D) + EPS);
;         GAS v2u* o8 = (GAS v2u*)(HN + (size_t)r * D) + F.lane;
; #pragma unroll
;         for (int j = 0; j < 8; ++j) {
;             float rs = rs_all; f32x4 gn = {1.f, 1.f, 1.f, 1.f};
;             if (!HG) rs = 1.0f / sqrtf(wave_sum(ssj[j]) * (1.0f / 256.0f) + EPS);
;             else gn = *(const GAS f32x4*)(gain + 256 * j + 4 * F.lane);
;             const v2u gw2 = EW_NT ? __builtin_nontemporal_load(g8 + 64 * j) : g8[64 * j];
;             const f32x4 gt = {bflo(gw2.x), bfhi(gw2.x), bflo(gw2.y), bfhi(gw2.y)};
;             const f32x4 y = (v[j] * rs) * gn * gt;
;             v2u w; w.x = pk2(y[0], y[1]); w.y = pk2(y[2], y[3]); o8[64 * j] = w; }
;     }
.LBB0_574:
	v_lshl_add_u64 v[50:51], v[18:19], 0, v[0:1]
	v_add_co_u32_e32 v2, vcc, 0xf7800000, v50
	v_lshl_add_u64 v[20:21], v[50:51], 0, s[52:53]
	s_nop 0
	v_addc_co_u32_e32 v3, vcc, -1, v51, vcc
	global_load_dwordx2 v[2:3], v[2:3], off nt
	s_nop 0
	global_load_dwordx2 v[4:5], v[50:51], off nt
	s_mov_b32 s8, 0xf3400000
	s_mov_b32 s9, -1
	s_add_i32 s6, s6, s42
	v_lshl_add_u64 v[18:19], v[18:19], 0, s[74:75]
	s_cmp_lt_i32 s6, s47
	s_waitcnt vmcnt(1)
	v_lshlrev_b32_e32 v22, 16, v2
	v_and_b32_e32 v23, 0xffff0000, v2
	s_waitcnt vmcnt(0)
	v_lshlrev_b32_e32 v24, 16, v4
	v_and_b32_e32 v25, 0xffff0000, v4
	v_lshlrev_b32_e32 v2, 16, v3
	v_and_b32_e32 v3, 0xffff0000, v3
	v_lshlrev_b32_e32 v4, 16, v5
	v_and_b32_e32 v5, 0xffff0000, v5
	v_add_f32_e32 v54, v2, v4
	v_add_f32_e32 v55, v3, v5
	global_load_dwordx2 v[4:5], v[20:21], off offset:512 nt
	global_load_dwordx2 v[26:27], v[50:51], off offset:512 nt
	global_load_dwordx2 v[30:31], v[20:21], off offset:1024 nt
	global_load_dwordx2 v[32:33], v[50:51], off offset:1024 nt
	v_mul_f32_e32 v2, v55, v55
	v_add_f32_e32 v52, v22, v24
	v_add_f32_e32 v53, v23, v25
	v_fma_f32 v24, v54, v54, v2
	v_fma_f32 v25, v55, v55, v2
	v_mul_f32_e32 v22, v52, v52
	v_mul_f32_e32 v23, v53, v53
	s_waitcnt vmcnt(3)
	v_lshlrev_b32_e32 v2, 16, v4
	v_and_b32_e32 v3, 0xffff0000, v4
	s_waitcnt vmcnt(2)
	v_lshlrev_b32_e32 v28, 16, v26
	v_and_b32_e32 v29, 0xffff0000, v26
	v_add_f32_e32 v2, v2, v28
	v_add_f32_e32 v3, v3, v29
	v_lshlrev_b32_e32 v26, 16, v27
	v_mul_f32_e32 v4, v3, v3
	v_fma_f32 v28, v2, v2, v4
	v_fma_f32 v29, v3, v3, v4
	v_lshlrev_b32_e32 v4, 16, v5
	v_and_b32_e32 v5, 0xffff0000, v5
	v_and_b32_e32 v27, 0xffff0000, v27
	v_add_f32_e32 v44, v4, v26
	v_add_f32_e32 v45, v5, v27
	s_waitcnt vmcnt(1)
	v_lshlrev_b32_e32 v34, 16, v30
	v_mul_f32_e32 v4, v45, v45
	v_fma_f32 v26, v44, v44, v4
	v_fma_f32 v27, v45, v45, v4
	s_waitcnt vmcnt(0)
	v_lshlrev_b32_e32 v4, 16, v32
	v_and_b32_e32 v5, 0xffff0000, v32
	v_and_b32_e32 v35, 0xffff0000, v30
	v_add_f32_e32 v4, v34, v4
	v_add_f32_e32 v5, v35, v5
	v_lshlrev_b32_e32 v32, 16, v33
	v_lshlrev_b32_e32 v30, 16, v31
	v_and_b32_e32 v33, 0xffff0000, v33
	v_and_b32_e32 v31, 0xffff0000, v31
	v_add_f32_e32 v40, v30, v32
	v_add_f32_e32 v41, v31, v33
	v_pk_mov_b32 v[22:23], v[22:23], v[4:5] op_sel:[1,0]
	v_mul_f32_e32 v30, v4, v4
	v_mul_f32_e32 v31, v5, v5
	v_mul_f32_e32 v32, v40, v40
	v_mul_f32_e32 v33, v41, v41
	v_fma_f32 v34, v52, v52, v22
	v_fma_f32 v35, v53, v53, v23
	v_mul_f32_e32 v22, v4, v22
	v_mul_f32_e32 v23, v4, v23
	v_mov_b32_e32 v35, v23
	v_mov_b32_e32 v25, v31
	v_mov_b32_e32 v29, v32
	v_mov_b32_e32 v27, v33
	v_add_f32_e32 v22, v34, v24
	v_add_f32_e32 v23, v35, v25
	v_add_f32_e32 v24, v28, v26
	v_add_f32_e32 v25, v29, v27
	s_nop 0
	v_add_f32_e32 v22, v22, v24
	v_add_f32_e32 v23, v23, v25
	global_load_dwordx2 v[24:25], v[20:21], off offset:1536 nt
	global_load_dwordx2 v[26:27], v[50:51], off offset:1536 nt
	v_pk_add_f32 v[22:23], v[22:23], v[22:23] op_sel:[0,1] op_sel_hi:[1,0]
	s_waitcnt vmcnt(1)
	v_lshlrev_b32_e32 v29, 16, v25
	v_lshlrev_b32_e32 v28, 16, v24
	s_waitcnt vmcnt(0)
	v_lshlrev_b32_e32 v31, 16, v27
	v_lshlrev_b32_e32 v30, 16, v26
	v_and_b32_e32 v25, 0xffff0000, v25
	v_and_b32_e32 v24, 0xffff0000, v24
	v_and_b32_e32 v27, 0xffff0000, v27
	v_and_b32_e32 v26, 0xffff0000, v26
	v_add_f32_e32 v42, v28, v30
	v_add_f32_e32 v43, v29, v31
	v_add_f32_e32 v46, v24, v26
	v_add_f32_e32 v47, v25, v27
	global_load_dwordx2 v[26:27], v[20:21], off offset:2048 nt
	global_load_dwordx2 v[28:29], v[50:51], off offset:2048 nt
	v_mul_f32_e32 v24, v46, v46
	v_mul_f32_e32 v25, v47, v47
	s_waitcnt vmcnt(1)
	v_lshlrev_b32_e32 v30, 16, v26
	v_and_b32_e32 v31, 0xffff0000, v26
	s_waitcnt vmcnt(0)
	v_lshlrev_b32_e32 v32, 16, v28
	v_and_b32_e32 v33, 0xffff0000, v28
	v_add_f32_e32 v38, v30, v32
	v_add_f32_e32 v39, v31, v33
	v_lshlrev_b32_e32 v28, 16, v29
	v_mul_f32_e32 v26, v39, v39
	v_fma_f32 v34, v38, v38, v26
	v_fma_f32 v35, v39, v39, v26
	v_lshlrev_b32_e32 v26, 16, v27
	v_and_b32_e32 v27, 0xffff0000, v27
	v_and_b32_e32 v29, 0xffff0000, v29
	v_add_f32_e32 v48, v26, v28
	v_add_f32_e32 v49, v27, v29
	v_fma_f32 v24, v42, v42, v24
	v_fma_f32 v25, v43, v43, v25
	v_mul_f32_e32 v26, v49, v49
	v_fma_f32 v36, v48, v48, v26
	v_fma_f32 v37, v49, v49, v26
	global_load_dwordx2 v[26:27], v[20:21], off offset:2560 nt
	global_load_dwordx2 v[28:29], v[50:51], off offset:2560 nt
	v_pk_add_f32 v[24:25], v[24:25], v[24:25] op_sel:[0,1] op_sel_hi:[1,0]
	s_waitcnt vmcnt(1)
	v_lshlrev_b32_e32 v32, 16, v26
	s_waitcnt vmcnt(0)
	v_lshlrev_b32_e32 v30, 16, v28
	v_and_b32_e32 v31, 0xffff0000, v28
	v_and_b32_e32 v33, 0xffff0000, v26
	v_lshlrev_b32_e32 v28, 16, v29
	v_lshlrev_b32_e32 v26, 16, v27
	v_and_b32_e32 v29, 0xffff0000, v29
	v_and_b32_e32 v27, 0xffff0000, v27
	v_add_f32_e32 v30, v32, v30
	v_add_f32_e32 v31, v33, v31
	v_add_f32_e32 v32, v26, v28
	v_add_f32_e32 v33, v27, v29
	global_load_dwordx2 v[28:29], v[20:21], off offset:3072 nt
	global_load_dwordx2 v[60:61], v[50:51], off offset:3072 nt
	s_nop 0
	global_load_dwordx2 v[20:21], v[20:21], off offset:3584 nt
	s_nop 0
	global_load_dwordx2 v[64:65], v[50:51], off offset:3584 nt
	v_mul_f32_e32 v56, v30, v30
	v_mul_f32_e32 v57, v31, v31
	v_mul_f32_e32 v58, v32, v32
	v_mul_f32_e32 v59, v33, v33
	v_mov_b32_e32 v66, v56
	v_mov_b32_e32 v68, v57
	s_waitcnt vmcnt(3)
	v_lshlrev_b32_e32 v26, 16, v28
	v_and_b32_e32 v27, 0xffff0000, v28
	s_waitcnt vmcnt(2)
	v_lshlrev_b32_e32 v62, 16, v60
	v_and_b32_e32 v63, 0xffff0000, v60
	v_add_f32_e32 v26, v26, v62
	v_add_f32_e32 v27, v27, v63
	s_waitcnt vmcnt(1)
	v_lshlrev_b32_e32 v35, 16, v20
	v_mul_f32_e32 v28, v27, v27
	s_waitcnt vmcnt(0)
; #define GAS __attribute__((address_space(1)))
; __device__ __forceinline__ unsigned pk2(float lo, float hi) { const f32x2_t v = {lo, hi}; const bf16x2_t b = __builtin_convertvector(v, bf16x2_t); return __builtin_bit_cast(unsigned, b); }
; template <bool HG>
; __device__ __forceinline__ void readout_phase(const Args& a, Frame& F, const float* gain, int nrows) {
;     ...
;         for (int j = 0; j < 8; ++j) { const v2u fa = EW_NT ? __builtin_nontemporal_load(f + 64 * j) : f[64 * j], fb = EW_NT ? __builtin_nontemporal_load(bk + 64 * j) : bk[64 * j]; v[j] = (f32x4){bflo(fa.x) + bflo(fb.x), bfhi(fa.x) + bfhi(fb.x), bflo(fa.y) + bflo(fb.y), bfhi(fa.y) + bfhi(fb.y)}; ssj[j] = (v[j][0] * v[j][0] + v[j][1] * v[j][1]) + (v[j][2] * v[j][2] + v[j][3] * v[j][3]); tot += ssj[j]; }
;         float rs_all = 0.f;
;         if (HG) rs_all = 1.0f / sqrtf(wave_sum(tot) * (1.0f / D) + EPS);
;         GAS v2u* o8 = (GAS v2u*)(HN + (size_t)r * D) + F.lane;
; #pragma unroll
;         for (int j = 0; j < 8; ++j) {
;             float rs = rs_all; f32x4 gn = {1.f, 1.f, 1.f, 1.f};
;             if (!HG) rs = 1.0f / sqrtf(wave_sum(ssj[j]) * (1.0f / 256.0f) + EPS);
;             else gn = *(const GAS f32x4*)(gain + 256 * j + 4 * F.lane);
;             const v2u gw2 = EW_NT ? __builtin_nontemporal_load(g8 + 64 * j) : g8[64 * j];
;             const f32x4 gt = {bflo(gw2.x), bfhi(gw2.x), bflo(gw2.y), bfhi(gw2.y)};
;             const f32x4 y = (v[j] * rs) * gn * gt;
;             v2u w; w.x = pk2(y[0], y[1]); w.y = pk2(y[2], y[3]); o8[64 * j] = w; }
	v_lshlrev_b32_e32 v37, 16, v64
	v_fma_f32 v62, v26, v26, v28
	v_fma_f32 v63, v27, v27, v28
	v_lshlrev_b32_e32 v28, 16, v29
	v_and_b32_e32 v29, 0xffff0000, v29
	v_lshlrev_b32_e32 v60, 16, v61
	v_and_b32_e32 v61, 0xffff0000, v61
	v_and_b32_e32 v67, 0xffff0000, v20
	v_and_b32_e32 v69, 0xffff0000, v64
	v_mov_b32_e32 v23, v35
	v_mov_b32_e32 v25, v37
	v_add_f32_e32 v28, v28, v60
	v_add_f32_e32 v29, v29, v61
	v_lshlrev_b32_e32 v64, 16, v65
	v_lshlrev_b32_e32 v20, 16, v21
	v_and_b32_e32 v65, 0xffff0000, v65
	v_and_b32_e32 v21, 0xffff0000, v21
	v_add_f32_e32 v22, v22, v24
	v_add_f32_e32 v23, v23, v25
	v_add_f32_e32 v34, v34, v36
	v_add_f32_e32 v35, v35, v37
	v_add_f32_e32 v24, v66, v68
	v_add_f32_e32 v25, v67, v69
	v_mov_b32_e32 v66, v58
	v_mov_b32_e32 v68, v59
	v_mul_f32_e32 v60, v29, v29
	v_add_f32_e32 v20, v20, v64
	v_add_f32_e32 v21, v21, v65
	v_add_f32_e32 v36, v66, v68
	v_add_f32_e32 v37, v67, v69
	v_add_f32_e32 v56, v22, v34
	v_add_f32_e32 v57, v23, v35
	v_mul_f32_e32 v34, v22, v34
	v_mul_f32_e32 v35, v23, v35
	v_fma_f32 v61, v29, v29, v60
	v_fma_f32 v60, v28, v28, v60
	v_mul_f32_e32 v64, v20, v20
	v_mul_f32_e32 v65, v21, v21
	v_mov_b32_e32 v57, v35
	v_add_f32_e32 v34, v24, v36
	v_add_f32_e32 v35, v25, v37
	v_mul_f32_e32 v36, v24, v36
	v_mul_f32_e32 v37, v25, v37
	v_mov_b32_e32 v63, v64
	v_mov_b32_e32 v35, v37
	v_mov_b32_e32 v61, v65
	v_add_f32_e32 v34, v56, v34
	v_add_f32_e32 v35, v57, v35
	v_add_f32_e32 v36, v62, v60
	v_add_f32_e32 v37, v63, v61
	s_nop 0
	v_add_f32_e32 v34, v34, v36
	v_add_f32_e32 v35, v35, v37
	s_nop 0
	v_add_f32_e32 v22, v34, v35
	v_lshl_add_u64 v[34:35], v[50:51], 0, s[8:9]
	s_nop 0
	v_add_f32_dpp v22, v22, v22 quad_perm:[1,0,3,2] row_mask:0xf bank_mask:0xf bound_ctrl:1
	s_nop 1
	v_add_f32_dpp v22, v22, v22 quad_perm:[2,3,0,1] row_mask:0xf bank_mask:0xf bound_ctrl:1
	s_nop 1
	v_add_f32_dpp v22, v22, v22 row_half_mirror row_mask:0xf bank_mask:0xf bound_ctrl:1
	s_nop 1
	v_add_f32_dpp v22, v22, v22 row_mirror row_mask:0xf bank_mask:0xf bound_ctrl:1
	s_nop 0
	v_readlane_b32 s7, v22, 16
	v_readlane_b32 s10, v22, 48
	v_readlane_b32 s8, v22, 0
	v_readlane_b32 s9, v22, 32
	v_mov_b32_e32 v36, s7
	v_mov_b32_e32 v37, s10
	v_add_f32_e32 v36, s8, v36
	v_add_f32_e32 v37, s9, v37
	s_mov_b32 s7, 0xf3400000
	v_add_f32_e32 v22, v36, v37
	v_fmamk_f32 v22, v22, 0x3a000000, v252
	v_cmp_gt_f32_e32 vcc, s55, v22
	v_mul_f32_e32 v24, 0x4f800000, v22
	s_nop 0
	v_cndmask_b32_e32 v22, v22, v24, vcc
	v_sqrt_f32_e32 v24, v22
	s_nop 0
	v_add_u32_e32 v36, -1, v24
	v_fma_f32 v37, -v36, v24, v22
	v_cmp_ge_f32_e64 s[8:9], 0, v37
	v_add_u32_e32 v37, 1, v24
	s_nop 0
	v_cndmask_b32_e64 v36, v24, v36, s[8:9]
	v_fma_f32 v24, -v37, v24, v22
	v_cmp_lt_f32_e64 s[8:9], 0, v24
	s_nop 1
	v_cndmask_b32_e64 v24, v36, v37, s[8:9]
	v_mul_f32_e32 v36, 0x37800000, v24
	v_cndmask_b32_e32 v24, v24, v36, vcc
	v_cmp_class_f32_e32 vcc, v22, v253
	s_nop 1
	v_cndmask_b32_e32 v22, v24, v22, vcc
	v_div_scale_f32 v24, s[8:9], v22, v22, 1.0
	v_rcp_f32_e32 v36, v24
	s_nop 0
	v_fma_f32 v37, -v24, v36, 1.0
	v_fmac_f32_e32 v36, v37, v36
	v_div_scale_f32 v37, vcc, 1.0, v22, 1.0
	v_mul_f32_e32 v56, v37, v36
	v_fma_f32 v57, -v24, v56, v37
	v_fmac_f32_e32 v56, v57, v36
	v_fma_f32 v24, -v24, v56, v37
	v_div_fmas_f32 v24, v24, v36, v56
	v_add_co_u32_e32 v60, vcc, s7, v50
	global_load_dwordx4 v[56:59], v[8:9], off
	s_nop 0
	v_addc_co_u32_e32 v61, vcc, -1, v51, vcc
	global_load_dwordx2 v[60:61], v[60:61], off nt
	v_div_fixup_f32 v22, v24, v22, 1.0
	v_mul_f32_e32 v54, v54, v22
	v_mul_f32_e32 v55, v55, v22
	v_mul_f32_e32 v52, v52, v22
	v_mul_f32_e32 v53, v53, v22
	v_lshl_add_u64 v[36:37], v[50:51], 0, s[12:13]
	v_add_co_u32_e32 v50, vcc, s67, v50
	v_mul_f32_e32 v44, v44, v22
	v_mul_f32_e32 v45, v45, v22
	s_nop 0
	v_addc_co_u32_e32 v51, vcc, -1, v51, vcc
	v_mul_f32_e32 v2, v2, v22
	v_mul_f32_e32 v3, v3, v22
	v_mul_f32_e32 v40, v40, v22
	v_mul_f32_e32 v41, v41, v22
	v_mul_f32_e32 v4, v4, v22
	v_mul_f32_e32 v5, v5, v22
	v_mul_f32_e32 v38, v38, v22
	v_mul_f32_e32 v39, v39, v22
	v_mul_f32_e32 v32, v32, v22
	v_mul_f32_e32 v33, v33, v22
	v_mul_f32_e32 v30, v30, v22
	v_mul_f32_e32 v31, v31, v22
	v_mul_f32_e32 v28, v28, v22
	v_mul_f32_e32 v29, v29, v22
	v_mul_f32_e32 v26, v26, v22
	v_mul_f32_e32 v27, v27, v22
	v_mov_b32_e32 v24, v23
	v_mul_f32_e32 v20, v20, v22
	v_mul_f32_e32 v21, v21, v22
	s_waitcnt vmcnt(1)
	v_mul_f32_e32 v52, v56, v52
	v_mul_f32_e32 v53, v57, v53
	v_mul_f32_e32 v54, v58, v54
	v_mul_f32_e32 v55, v59, v55
	s_waitcnt vmcnt(0)
	v_lshlrev_b32_e32 v62, 16, v60
	v_and_b32_e32 v63, 0xffff0000, v60
	v_lshlrev_b32_e32 v60, 16, v61
	v_and_b32_e32 v61, 0xffff0000, v61
	v_mul_f32_e32 v54, v54, v60
	v_mul_f32_e32 v55, v55, v61
	v_mul_f32_e32 v52, v52, v62
	v_mul_f32_e32 v53, v53, v63
	s_nop 0
	v_cvt_pk_bf16_f32 v52, v52, v53
	v_cvt_pk_bf16_f32 v53, v54, v55
	global_store_dwordx2 v[50:51], v[52:53], off
	global_load_dwordx4 v[50:53], v[8:9], off offset:1024
	s_nop 0
	global_load_dwordx2 v[54:55], v[34:35], off offset:512 nt
	s_waitcnt vmcnt(1)
; #define GAS __attribute__((address_space(1)))
; __device__ __forceinline__ unsigned pk2(float lo, float hi) { const f32x2_t v = {lo, hi}; const bf16x2_t b = __builtin_convertvector(v, bf16x2_t); return __builtin_bit_cast(unsigned, b); }
; template <bool HG>
; __device__ __forceinline__ void readout_phase(const Args& a, Frame& F, const float* gain, int nrows) {
;     ...
;         for (int j = 0; j < 8; ++j) {
;             float rs = rs_all; f32x4 gn = {1.f, 1.f, 1.f, 1.f};
;             if (!HG) rs = 1.0f / sqrtf(wave_sum(ssj[j]) * (1.0f / 256.0f) + EPS);
;             else gn = *(const GAS f32x4*)(gain + 256 * j + 4 * F.lane);
;             const v2u gw2 = EW_NT ? __builtin_nontemporal_load(g8 + 64 * j) : g8[64 * j];
;             const f32x4 gt = {bflo(gw2.x), bfhi(gw2.x), bflo(gw2.y), bfhi(gw2.y)};
;             const f32x4 y = (v[j] * rs) * gn * gt;
;             v2u w; w.x = pk2(y[0], y[1]); w.y = pk2(y[2], y[3]); o8[64 * j] = w; }
	v_mul_f32_e32 v2, v50, v2
	v_mul_f32_e32 v3, v51, v3
	s_waitcnt vmcnt(0)
	v_lshlrev_b32_e32 v56, 16, v54
	v_and_b32_e32 v57, 0xffff0000, v54
	v_lshlrev_b32_e32 v54, 16, v55
	v_and_b32_e32 v55, 0xffff0000, v55
	v_mul_f32_e32 v44, v52, v44
	v_mul_f32_e32 v45, v53, v45
	v_mul_f32_e32 v2, v2, v56
	v_mul_f32_e32 v3, v3, v57
	v_mul_f32_e32 v44, v44, v54
	v_mul_f32_e32 v45, v45, v55
	v_cvt_pk_bf16_f32 v2, v2, v3
	v_cvt_pk_bf16_f32 v3, v44, v45
	global_store_dwordx2 v[36:37], v[2:3], off offset:512
	global_load_dwordx4 v[50:53], v[8:9], off offset:2048
	s_nop 0
	global_load_dwordx2 v[2:3], v[34:35], off offset:1024 nt
	s_waitcnt vmcnt(1)
	v_mul_f32_e32 v4, v50, v4
	v_mul_f32_e32 v5, v51, v5
	s_waitcnt vmcnt(0)
	v_lshlrev_b32_e32 v44, 16, v2
	v_and_b32_e32 v45, 0xffff0000, v2
	v_lshlrev_b32_e32 v2, 16, v3
	v_and_b32_e32 v3, 0xffff0000, v3
	v_mul_f32_e32 v40, v52, v40
	v_mul_f32_e32 v41, v53, v41
	v_mul_f32_e32 v4, v4, v44
	v_mul_f32_e32 v5, v5, v45
	v_mul_f32_e32 v2, v40, v2
	v_mul_f32_e32 v3, v41, v3
	v_cvt_pk_bf16_f32 v4, v4, v5
	v_cvt_pk_bf16_f32 v5, v2, v3
	global_store_dwordx2 v[36:37], v[4:5], off offset:1024
	global_load_dwordx4 v[2:5], v[8:9], off offset:3072
	s_nop 0
	global_load_dwordx2 v[40:41], v[34:35], off offset:1536 nt
	v_mov_b32_e32 v50, v43
	v_mov_b32_e32 v51, v47
	v_mov_b32_e32 v43, v46
	v_mul_f32_e32 v50, v50, v22
	v_mul_f32_e32 v51, v51, v22
	v_mul_f32_e32 v42, v42, v22
	v_mul_f32_e32 v43, v43, v22
	s_waitcnt vmcnt(1)
	v_mul_f32_e32 v4, v50, v4
	v_mul_f32_e32 v5, v51, v5
	s_waitcnt vmcnt(0)
	v_lshlrev_b32_e32 v44, 16, v40
	v_and_b32_e32 v45, 0xffff0000, v40
	v_lshlrev_b32_e32 v40, 16, v41
	v_and_b32_e32 v41, 0xffff0000, v41
	v_mul_f32_e32 v2, v42, v2
	v_mul_f32_e32 v3, v43, v3
	v_mul_f32_e32 v4, v4, v40
	v_mul_f32_e32 v5, v5, v41
	v_mul_f32_e32 v2, v2, v44
	v_mul_f32_e32 v3, v3, v45
	v_mul_f32_e32 v44, v48, v22
	v_mul_f32_e32 v45, v49, v22
	v_cvt_pk_bf16_f32 v2, v2, v3
	v_cvt_pk_bf16_f32 v3, v4, v5
	global_store_dwordx2 v[36:37], v[2:3], off offset:1536
	global_load_dwordx4 v[2:5], v[10:11], off
	s_nop 0
	global_load_dwordx2 v[40:41], v[34:35], off offset:2048 nt
	v_mul_f32_e32 v23, v25, v22
	v_mul_f32_e32 v22, v24, v22
	s_waitcnt vmcnt(1)
	v_mul_f32_e32 v2, v38, v2
	v_mul_f32_e32 v3, v39, v3
	s_waitcnt vmcnt(0)
	v_lshlrev_b32_e32 v42, 16, v40
	v_and_b32_e32 v43, 0xffff0000, v40
	v_lshlrev_b32_e32 v40, 16, v41
	v_and_b32_e32 v41, 0xffff0000, v41
	v_mul_f32_e32 v4, v44, v4
	v_mul_f32_e32 v5, v45, v5
	v_mul_f32_e32 v2, v2, v42
	v_mul_f32_e32 v3, v3, v43
	v_mul_f32_e32 v4, v4, v40
	v_mul_f32_e32 v5, v5, v41
	v_cvt_pk_bf16_f32 v2, v2, v3
	v_cvt_pk_bf16_f32 v3, v4, v5
	global_store_dwordx2 v[36:37], v[2:3], off offset:2048
	global_load_dwordx4 v[2:5], v[12:13], off
	s_nop 0
	global_load_dwordx2 v[38:39], v[34:35], off offset:2560 nt
	s_waitcnt vmcnt(1)
	v_mul_f32_e32 v2, v30, v2
	v_mul_f32_e32 v3, v31, v3
	s_waitcnt vmcnt(0)
	v_lshlrev_b32_e32 v40, 16, v38
	v_and_b32_e32 v41, 0xffff0000, v38
	v_lshlrev_b32_e32 v38, 16, v39
	v_and_b32_e32 v39, 0xffff0000, v39
	v_mul_f32_e32 v4, v32, v4
	v_mul_f32_e32 v5, v33, v5
	v_mul_f32_e32 v2, v2, v40
	v_mul_f32_e32 v3, v3, v41
	v_mul_f32_e32 v4, v4, v38
	v_mul_f32_e32 v5, v5, v39
	v_cvt_pk_bf16_f32 v2, v2, v3
	v_cvt_pk_bf16_f32 v3, v4, v5
	global_store_dwordx2 v[36:37], v[2:3], off offset:2560
	global_load_dwordx4 v[2:5], v[14:15], off
	s_nop 0
	global_load_dwordx2 v[30:31], v[34:35], off offset:3072 nt
	s_waitcnt vmcnt(1)
	v_mul_f32_e32 v2, v26, v2
	v_mul_f32_e32 v3, v27, v3
	s_waitcnt vmcnt(0)
	v_lshlrev_b32_e32 v32, 16, v30
	v_and_b32_e32 v33, 0xffff0000, v30
	v_lshlrev_b32_e32 v30, 16, v31
	v_and_b32_e32 v31, 0xffff0000, v31
	v_mul_f32_e32 v4, v28, v4
	v_mul_f32_e32 v5, v29, v5
	v_mul_f32_e32 v2, v2, v32
	v_mul_f32_e32 v3, v3, v33
	v_mul_f32_e32 v4, v4, v30
	v_mul_f32_e32 v5, v5, v31
	v_cvt_pk_bf16_f32 v2, v2, v3
	v_cvt_pk_bf16_f32 v3, v4, v5
	global_store_dwordx2 v[36:37], v[2:3], off offset:3072
	global_load_dwordx4 v[2:5], v[16:17], off
	s_nop 0
	global_load_dwordx2 v[26:27], v[34:35], off offset:3584 nt
	s_waitcnt vmcnt(1)
	v_mul_f32_e32 v2, v22, v2
	v_mul_f32_e32 v3, v23, v3
	s_waitcnt vmcnt(0)
	v_lshlrev_b32_e32 v28, 16, v26
	v_and_b32_e32 v29, 0xffff0000, v26
	v_lshlrev_b32_e32 v26, 16, v27
	v_and_b32_e32 v27, 0xffff0000, v27
	v_mul_f32_e32 v4, v20, v4
	v_mul_f32_e32 v5, v21, v5
	v_mul_f32_e32 v2, v2, v28
	v_mul_f32_e32 v3, v3, v29
	v_mul_f32_e32 v4, v4, v26
	v_mul_f32_e32 v5, v5, v27
	v_cvt_pk_bf16_f32 v2, v2, v3
	v_cvt_pk_bf16_f32 v3, v4, v5
	global_store_dwordx2 v[36:37], v[2:3], off offset:3584
	s_cbranch_scc1 .LBB0_574

; #define GAS __attribute__((address_space(1)))
; #define LAS __attribute__((address_space(3)))
; template <bool HG>
; __device__ __forceinline__ void readout_phase2(const Args& a, Frame& F, const float* gain, int nrows) {
;     ...
;     const int nw = F.vcu * NWAVES + F.wave;
;     const bf16* OF = (const bf16*)(a.ws + WS_OF); const bf16* OB = (const bf16*)(a.ws + WS_OB);
;     const bf16* G = (const bf16*)(a.ws + WS_ACT) + (size_t)(HG ? 6 : 3) * ACT_STRIDE; bf16* HN = (bf16*)(a.ws + WS_HN);
;     LAS float* GL = (LAS float*)F.lds;
;     v2u f0[8], b0[8], g0[8], f1[8], b1[8], g1[8], f2[8], b2[8], g2[8];
;     ...
;     RO_LOAD(f0, b0, g0, nw); RO_LOAD(f1, b1, g1, nw + 2048); RO_LOAD(f2, b2, g2, nw + 2 * 2048);
;     if (HG) { for (int q = F.tid; q < D / 4; q += NWAVES * 64) ((LAS f32x4*)GL)[q] = ((const GAS f32x4*)gain)[q];
.LBB0_576:
	s_andn2_b64 vcc, exec, s[8:9]
	s_cbranch_vccnz .LBB0_583
	s_getreg_b32 s6, hwreg(HW_REG_HW_ID, 0, 6)
	s_lshl_b32 s6, s6, 2
	s_add_i32 s6, s6, 0
	s_add_i32 s6, s6, 0x20540
	v_mov_b32_e32 v0, s6
	ds_read_b32 v0, v0
	v_mov_b64_e32 v[2:3], s[0:1]
	s_waitcnt lgkmcnt(0)
	v_readfirstlane_b32 s6, v0
	v_mbcnt_lo_u32_b32 v0, -1, 0
	v_mbcnt_hi_u32_b32 v0, -1, v0
	s_nop 1
	v_lshl_add_u32 v100, s6, 6, v0
	v_mov_b32_e32 v2, s72
	v_mov_b32_e32 v3, s73
	v_readfirstlane_b32 s6, v100
	s_ashr_i32 s6, s6, 6
	s_add_i32 s10, s6, s91
	s_mov_b64 s[6:7], 0x2ac00000
	s_ashr_i32 s11, s10, 31
	v_and_b32_e32 v166, 63, v100
	v_lshlrev_b32_e32 v0, 3, v166
	s_add_i32 s8, s10, 0x800
	s_ashr_i32 s9, s8, 31
	s_add_i32 s12, s10, 0x1000
	s_ashr_i32 s13, s12, 31
	s_waitcnt vmcnt(0) lgkmcnt(0)
	v_lshl_add_u64 v[36:37], v[2:3], 0, s[6:7]
	s_mov_b64 s[6:7], 0x33400000
	v_lshl_add_u64 v[38:39], v[2:3], 0, s[6:7]
	s_mov_b64 s[6:7], 0x26800000
	v_lshl_add_u64 v[40:41], v[2:3], 0, s[6:7]
	s_lshl_b64 s[6:7], s[10:11], 12
	v_lshl_add_u64 v[8:9], v[38:39], 0, s[6:7]
	v_lshl_add_u64 v[4:5], v[36:37], 0, s[6:7]
	v_lshl_add_u64 v[42:43], v[8:9], 0, v[0:1]
	v_lshl_add_u64 v[8:9], v[40:41], 0, s[6:7]
	v_lshl_add_u64 v[4:5], v[4:5], 0, v[0:1]
	v_lshl_add_u64 v[44:45], v[8:9], 0, v[0:1]
	s_lshl_b64 s[6:7], s[8:9], 12
	v_lshl_add_u64 v[184:185], s[84:85], 2, v[6:7]
	v_mov_b32_e32 v186, v100
	v_mov_b32_e32 v187, 0
	v_lshl_add_u64 v[184:185], v[186:187], 4, v[184:185]
	global_load_dwordx4 v[188:191], v[184:185], off
	global_load_dwordx2 v[156:157], v[4:5], off nt
	global_load_dwordx2 v[154:155], v[42:43], off nt
	global_load_dwordx2 v[8:9], v[44:45], off nt
	global_load_dwordx2 v[152:153], v[4:5], off offset:512 nt
	global_load_dwordx2 v[150:151], v[42:43], off offset:512 nt
	global_load_dwordx2 v[10:11], v[44:45], off offset:512 nt
	global_load_dwordx2 v[148:149], v[4:5], off offset:1024 nt
	global_load_dwordx2 v[140:141], v[42:43], off offset:1024 nt
	global_load_dwordx2 v[14:15], v[44:45], off offset:1024 nt
	global_load_dwordx2 v[90:91], v[4:5], off offset:1536 nt
	global_load_dwordx2 v[80:81], v[42:43], off offset:1536 nt
	global_load_dwordx2 v[18:19], v[44:45], off offset:1536 nt
	global_load_dwordx2 v[34:35], v[4:5], off offset:2048 nt
	global_load_dwordx2 v[32:33], v[42:43], off offset:2048 nt
	global_load_dwordx2 v[22:23], v[44:45], off offset:2048 nt
	global_load_dwordx2 v[28:29], v[4:5], off offset:2560 nt
	global_load_dwordx2 v[24:25], v[42:43], off offset:2560 nt
	global_load_dwordx2 v[26:27], v[44:45], off offset:2560 nt
	global_load_dwordx2 v[20:21], v[4:5], off offset:3072 nt
	global_load_dwordx2 v[16:17], v[42:43], off offset:3072 nt
	global_load_dwordx2 v[30:31], v[44:45], off offset:3072 nt
	global_load_dwordx2 v[12:13], v[4:5], off offset:3584 nt
	s_nop 0
	global_load_dwordx2 v[4:5], v[42:43], off offset:3584 nt
	global_load_dwordx2 v[76:77], v[44:45], off offset:3584 nt
	v_lshl_add_u64 v[42:43], v[36:37], 0, s[6:7]
	v_lshl_add_u64 v[44:45], v[38:39], 0, s[6:7]
	v_lshl_add_u64 v[42:43], v[42:43], 0, v[0:1]
	v_lshl_add_u64 v[48:49], v[44:45], 0, v[0:1]
	v_lshl_add_u64 v[44:45], v[40:41], 0, s[6:7]
	s_lshl_b64 s[6:7], s[12:13], 12
	v_lshl_add_u64 v[50:51], v[44:45], 0, v[0:1]
	global_load_dwordx2 v[146:147], v[42:43], off nt
	global_load_dwordx2 v[144:145], v[48:49], off nt
	global_load_dwordx2 v[72:73], v[50:51], off nt
	global_load_dwordx2 v[142:143], v[42:43], off offset:512 nt
	global_load_dwordx2 v[138:139], v[48:49], off offset:512 nt
	global_load_dwordx2 v[70:71], v[50:51], off offset:512 nt
	global_load_dwordx2 v[128:129], v[42:43], off offset:1024 nt
	global_load_dwordx2 v[126:127], v[48:49], off offset:1024 nt
	global_load_dwordx2 v[66:67], v[50:51], off offset:1024 nt
	global_load_dwordx2 v[120:121], v[42:43], off offset:1536 nt
	global_load_dwordx2 v[118:119], v[48:49], off offset:1536 nt
	global_load_dwordx2 v[60:61], v[50:51], off offset:1536 nt
	global_load_dwordx2 v[108:109], v[42:43], off offset:2048 nt
	global_load_dwordx2 v[106:107], v[48:49], off offset:2048 nt
	global_load_dwordx2 v[54:55], v[50:51], off offset:2048 nt
	global_load_dwordx2 v[98:99], v[42:43], off offset:2560 nt
	global_load_dwordx2 v[96:97], v[48:49], off offset:2560 nt
	global_load_dwordx2 v[46:47], v[50:51], off offset:2560 nt
	global_load_dwordx2 v[84:85], v[42:43], off offset:3072 nt
	global_load_dwordx2 v[82:83], v[48:49], off offset:3072 nt
	global_load_dwordx2 v[44:45], v[50:51], off offset:3072 nt
	global_load_dwordx2 v[78:79], v[42:43], off offset:3584 nt
	global_load_dwordx2 v[74:75], v[48:49], off offset:3584 nt
	s_nop 0
	global_load_dwordx2 v[42:43], v[50:51], off offset:3584 nt
	v_lshl_add_u64 v[48:49], v[36:37], 0, s[6:7]
	v_lshl_add_u64 v[86:87], v[48:49], 0, v[0:1]
	v_lshl_add_u64 v[48:49], v[38:39], 0, s[6:7]
	v_lshl_add_u64 v[50:51], v[48:49], 0, v[0:1]
	v_lshl_add_u64 v[48:49], v[40:41], 0, s[6:7]
	v_lshl_add_u64 v[158:159], v[48:49], 0, v[0:1]
	global_load_dwordx2 v[136:137], v[86:87], off nt
	global_load_dwordx2 v[134:135], v[50:51], off nt
	global_load_dwordx2 v[68:69], v[158:159], off nt
	global_load_dwordx2 v[132:133], v[86:87], off offset:512 nt
	global_load_dwordx2 v[130:131], v[50:51], off offset:512 nt
	global_load_dwordx2 v[64:65], v[158:159], off offset:512 nt
	global_load_dwordx2 v[124:125], v[86:87], off offset:1024 nt
	global_load_dwordx2 v[122:123], v[50:51], off offset:1024 nt
	global_load_dwordx2 v[58:59], v[158:159], off offset:1024 nt
	global_load_dwordx2 v[114:115], v[86:87], off offset:1536 nt
	global_load_dwordx2 v[116:117], v[50:51], off offset:1536 nt
	global_load_dwordx2 v[62:63], v[158:159], off offset:1536 nt
	global_load_dwordx2 v[112:113], v[86:87], off offset:2048 nt
	global_load_dwordx2 v[110:111], v[50:51], off offset:2048 nt
	global_load_dwordx2 v[56:57], v[158:159], off offset:2048 nt
	global_load_dwordx2 v[104:105], v[86:87], off offset:2560 nt
	global_load_dwordx2 v[102:103], v[50:51], off offset:2560 nt
	global_load_dwordx2 v[52:53], v[158:159], off offset:2560 nt
	global_load_dwordx2 v[94:95], v[86:87], off offset:3072 nt
	global_load_dwordx2 v[92:93], v[50:51], off offset:3072 nt
	global_load_dwordx2 v[48:49], v[158:159], off offset:3072 nt
	s_nop 0
	global_load_dwordx2 v[86:87], v[86:87], off offset:3584 nt
	s_nop 0
	global_load_dwordx2 v[88:89], v[50:51], off offset:3584 nt
	s_nop 0
	global_load_dwordx2 v[50:51], v[158:159], off offset:3584 nt
	s_waitcnt vmcnt(62)
; #define GAS __attribute__((address_space(1)))
; #define LAS __attribute__((address_space(3)))
; template <bool HG>
; __device__ __forceinline__ void readout_phase2(const Args& a, Frame& F, const float* gain, int nrows) {
;     ...
;     if (HG) { for (int q = F.tid; q < D / 4; q += NWAVES * 64) ((LAS f32x4*)GL)[q] = ((const GAS f32x4*)gain)[q];
	v_lshl_add_u32 v184, v100, 4, 0
	ds_write_b128 v184, v[188:191]
	s_waitcnt vmcnt(62)
	v_lshlrev_b32_e32 v6, 16, v156
	v_and_b32_e32 v7, 0xffff0000, v156
	v_lshlrev_b32_e32 v100, 16, v154
	v_and_b32_e32 v101, 0xffff0000, v154
	v_add_f32_e32 v6, v6, v100
	v_add_f32_e32 v7, v7, v101
	v_lshlrev_b32_e32 v100, 16, v157
	v_and_b32_e32 v101, 0xffff0000, v157
	v_lshlrev_b32_e32 v154, 16, v155
	v_and_b32_e32 v155, 0xffff0000, v155
	v_add_f32_e32 v154, v100, v154
	v_add_f32_e32 v155, v101, v155
	v_lshlrev_b32_e32 v100, 16, v152
	v_and_b32_e32 v101, 0xffff0000, v152
	v_lshlrev_b32_e32 v156, 16, v150
	v_and_b32_e32 v157, 0xffff0000, v150
	v_add_f32_e32 v100, v100, v156
	v_add_f32_e32 v101, v101, v157
	v_lshlrev_b32_e32 v152, 16, v153
	v_and_b32_e32 v153, 0xffff0000, v153
	v_lshlrev_b32_e32 v150, 16, v151
	v_and_b32_e32 v151, 0xffff0000, v151
	v_add_f32_e32 v150, v152, v150
	v_add_f32_e32 v151, v153, v151
	v_mov_b32_e32 v156, v7
	v_mov_b32_e32 v157, v101
	v_mov_b32_e32 v152, v6
	v_mov_b32_e32 v153, v100
	v_mul_f32_e32 v156, v156, v156
	v_mul_f32_e32 v157, v157, v157
	v_mov_b32_e32 v158, v155
	v_mov_b32_e32 v159, v151
	v_fma_f32 v152, v152, v152, v156
	v_fma_f32 v153, v153, v153, v157
	v_mov_b32_e32 v156, v154
	v_mov_b32_e32 v157, v150
	v_mul_f32_e32 v158, v158, v158
	v_mul_f32_e32 v159, v159, v159
	s_lshl_b64 s[18:19], s[8:9], 11
	v_fma_f32 v156, v156, v156, v158
	v_fma_f32 v157, v157, v157, v159
	s_waitcnt vmcnt(58)
	v_lshlrev_b32_e32 v158, 16, v32
	v_add_f32_e32 v152, v152, v156
	v_add_f32_e32 v153, v153, v157
	v_lshlrev_b32_e32 v156, 16, v140
	v_add_f32_e32 v160, v152, v153
	v_add_f32_e32 v161, v153, v152
	v_lshlrev_b32_e32 v152, 16, v148
	v_and_b32_e32 v153, 0xffff0000, v148
	v_and_b32_e32 v157, 0xffff0000, v140
	v_lshlrev_b32_e32 v148, 16, v149
	v_and_b32_e32 v149, 0xffff0000, v149
	v_lshlrev_b32_e32 v140, 16, v141
	v_and_b32_e32 v141, 0xffff0000, v141
	v_add_f32_e32 v152, v152, v156
	v_add_f32_e32 v153, v153, v157
	v_add_f32_e32 v156, v148, v140
	v_add_f32_e32 v157, v149, v141
	v_mov_b32_e32 v148, v153
	v_mov_b32_e32 v149, v157
	v_mov_b32_e32 v140, v152
	v_mov_b32_e32 v141, v156
	v_mul_f32_e32 v148, v148, v148
	v_mul_f32_e32 v149, v149, v149
	v_and_b32_e32 v159, 0xffff0000, v32
	v_fma_f32 v140, v140, v140, v148
	v_fma_f32 v141, v141, v141, v149
	v_lshlrev_b32_e32 v148, 16, v80
	v_add_f32_e32 v162, v140, v141
	v_add_f32_e32 v163, v141, v140
	v_lshlrev_b32_e32 v140, 16, v90
	v_and_b32_e32 v141, 0xffff0000, v90
	v_and_b32_e32 v149, 0xffff0000, v80
	v_add_f32_e32 v140, v140, v148
	v_add_f32_e32 v141, v141, v149
	v_lshlrev_b32_e32 v90, 16, v91
	v_and_b32_e32 v91, 0xffff0000, v91
	v_lshlrev_b32_e32 v80, 16, v81
	v_and_b32_e32 v81, 0xffff0000, v81
	v_add_f32_e32 v148, v90, v80
	v_add_f32_e32 v149, v91, v81
	v_mul_f32_e32 v80, v141, v141
	v_fma_f32 v90, v140, v140, v80
	v_fma_f32 v91, v141, v141, v80
	v_mul_f32_e32 v80, v149, v149
	v_fma_f32 v164, v148, v148, v80
	v_fma_f32 v165, v149, v149, v80
	v_lshlrev_b32_e32 v80, 16, v34
	v_and_b32_e32 v81, 0xffff0000, v34
	v_lshlrev_b32_e32 v34, 16, v35
	v_and_b32_e32 v35, 0xffff0000, v35
	v_lshlrev_b32_e32 v32, 16, v33
	v_and_b32_e32 v33, 0xffff0000, v33
	v_add_f32_e32 v80, v80, v158
	v_add_f32_e32 v81, v81, v159
	v_add_f32_e32 v158, v34, v32
	v_add_f32_e32 v159, v35, v33
	v_mul_f32_e32 v32, v80, v80
	v_mul_f32_e32 v33, v81, v81
	v_mul_f32_e32 v34, v158, v158
	v_mul_f32_e32 v35, v159, v159
	v_mov_b32_e32 v161, v32
	v_mov_b32_e32 v163, v33
	v_mov_b32_e32 v91, v34
	v_mov_b32_e32 v165, v35
	v_add_f32_e32 v32, v160, v162
	v_add_f32_e32 v33, v161, v163
	v_add_f32_e32 v34, v90, v164
	v_add_f32_e32 v35, v91, v165
	s_waitcnt vmcnt(55)
	v_lshlrev_b32_e32 v90, 16, v24
	v_add_f32_e32 v32, v32, v34
	v_add_f32_e32 v33, v33, v35
	v_and_b32_e32 v91, 0xffff0000, v24
	v_add_f32_e32 v34, v32, v33
	v_add_f32_e32 v35, v33, v32
	v_lshlrev_b32_e32 v32, 16, v28
	v_and_b32_e32 v33, 0xffff0000, v28
	v_lshlrev_b32_e32 v28, 16, v29
	v_and_b32_e32 v29, 0xffff0000, v29
	v_lshlrev_b32_e32 v24, 16, v25
	v_and_b32_e32 v25, 0xffff0000, v25
	v_add_f32_e32 v32, v32, v90
	v_add_f32_e32 v33, v33, v91
	v_add_f32_e32 v28, v28, v24
	v_add_f32_e32 v29, v29, v25
	v_mov_b32_e32 v90, v33
	v_mov_b32_e32 v91, v29
	v_mov_b32_e32 v24, v32
	v_mov_b32_e32 v25, v28
	v_mul_f32_e32 v90, v90, v90
	v_mul_f32_e32 v91, v91, v91
	s_waitcnt vmcnt(52)
	v_lshlrev_b32_e32 v160, 16, v16
	v_fma_f32 v24, v24, v24, v90
	v_fma_f32 v25, v25, v25, v91
	v_lshlrev_b32_e32 v90, 16, v20
	v_and_b32_e32 v91, 0xffff0000, v20
	v_and_b32_e32 v161, 0xffff0000, v16
	v_lshlrev_b32_e32 v20, 16, v21
	v_and_b32_e32 v21, 0xffff0000, v21
	v_lshlrev_b32_e32 v16, 16, v17
	v_and_b32_e32 v17, 0xffff0000, v17
	v_add_f32_e32 v160, v90, v160
	v_add_f32_e32 v161, v91, v161
	v_add_f32_e32 v164, v20, v16
	v_add_f32_e32 v165, v21, v17
	s_waitcnt vmcnt(50)
	v_lshlrev_b32_e32 v90, 16, v12
	v_and_b32_e32 v91, 0xffff0000, v12
	s_waitcnt vmcnt(49)
	v_lshlrev_b32_e32 v162, 16, v4
	v_and_b32_e32 v163, 0xffff0000, v4
	v_lshlrev_b32_e32 v12, 16, v13
	v_and_b32_e32 v13, 0xffff0000, v13
	v_lshlrev_b32_e32 v4, 16, v5
	v_and_b32_e32 v5, 0xffff0000, v5
	v_mul_f32_e32 v16, v161, v161
	v_mul_f32_e32 v20, v165, v165
	v_add_f32_e32 v90, v90, v162
	v_add_f32_e32 v91, v91, v163
	v_add_f32_e32 v162, v12, v4
	v_add_f32_e32 v163, v13, v5
	v_pk_add_f32 v[24:25], v[24:25], v[24:25] op_sel:[0,1] op_sel_hi:[1,0]
	v_fma_f32 v17, v161, v161, v16
	v_fma_f32 v16, v160, v160, v16
	v_fma_f32 v21, v165, v165, v20
	v_fma_f32 v20, v164, v164, v20
	v_mul_f32_e32 v4, v90, v90
	v_mul_f32_e32 v5, v91, v91
	v_mul_f32_e32 v12, v162, v162
	v_mul_f32_e32 v13, v163, v163
	v_mov_b32_e32 v35, v4
	v_mov_b32_e32 v25, v5
	v_mov_b32_e32 v17, v12
	v_mov_b32_e32 v21, v13
	v_add_f32_e32 v4, v34, v24
	v_add_f32_e32 v5, v35, v25
	v_add_f32_e32 v12, v16, v20
	v_add_f32_e32 v13, v17, v21
	s_waitcnt vmcnt(47)
	v_lshlrev_b32_e32 v172, 16, v146
	v_add_f32_e32 v4, v4, v12
	v_add_f32_e32 v5, v5, v13
	v_and_b32_e32 v173, 0xffff0000, v146
	v_add_f32_e32 v4, v4, v5
	s_waitcnt vmcnt(46)
	v_lshlrev_b32_e32 v176, 16, v144
	v_and_b32_e32 v177, 0xffff0000, v144
	v_add_f32_dpp v4, v4, v4 quad_perm:[1,0,3,2] row_mask:0xf bank_mask:0xf bound_ctrl:1
	v_lshlrev_b32_e32 v146, 16, v147
	v_and_b32_e32 v147, 0xffff0000, v147
	v_add_f32_dpp v4, v4, v4 quad_perm:[2,3,0,1] row_mask:0xf bank_mask:0xf bound_ctrl:1
	v_lshlrev_b32_e32 v144, 16, v145
	v_and_b32_e32 v145, 0xffff0000, v145
	v_add_f32_dpp v4, v4, v4 row_half_mirror row_mask:0xf bank_mask:0xf bound_ctrl:1
	v_add_f32_e32 v172, v172, v176
	v_add_f32_e32 v173, v173, v177
	v_add_f32_e32 v146, v146, v144
	v_add_f32_e32 v147, v147, v145
	v_add_f32_dpp v4, v4, v4 row_mirror row_mask:0xf bank_mask:0xf bound_ctrl:1
	s_waitcnt vmcnt(44)
	v_lshlrev_b32_e32 v144, 16, v142
	v_readlane_b32 s8, v4, 16
	v_readlane_b32 s9, v4, 48
	v_readlane_b32 s6, v4, 0
	v_readlane_b32 s7, v4, 32
	v_mov_b32_e32 v4, s8
	v_mov_b32_e32 v5, s9
	v_add_f32_e32 v4, s6, v4
	v_add_f32_e32 v5, s7, v5
	s_mov_b64 s[6:7], 0x8c00000
	v_add_f32_e32 v4, v4, v5
	v_fmamk_f32 v4, v4, 0x3a000000, v252
	v_mul_f32_e32 v5, 0x4f800000, v4
	v_cmp_gt_f32_e32 vcc, s55, v4
	v_lshl_add_u64 v[34:35], v[2:3], 0, s[6:7]
	v_and_b32_e32 v145, 0xffff0000, v142
	v_cndmask_b32_e32 v4, v4, v5, vcc
	v_sqrt_f32_e32 v5, v4
	s_waitcnt vmcnt(43)
	v_lshlrev_b32_e32 v176, 16, v138
	v_and_b32_e32 v177, 0xffff0000, v138
	v_add_f32_e32 v144, v144, v176
	v_add_f32_e32 v145, v145, v177
	v_add_u32_e32 v2, -1, v5
	v_fma_f32 v3, -v2, v5, v4
	v_cmp_ge_f32_e64 s[8:9], 0, v3
	v_add_u32_e32 v3, 1, v5
	v_lshlrev_b32_e32 v142, 16, v143
	v_cndmask_b32_e64 v2, v5, v2, s[8:9]
	v_fma_f32 v5, -v3, v5, v4
	v_cmp_lt_f32_e64 s[8:9], 0, v5
	v_and_b32_e32 v143, 0xffff0000, v143
	v_lshlrev_b32_e32 v138, 16, v139
	v_cndmask_b32_e64 v2, v2, v3, s[8:9]
	v_mul_f32_e32 v3, 0x37800000, v2
	v_cndmask_b32_e32 v2, v2, v3, vcc
	v_cmp_class_f32_e32 vcc, v4, v253
	v_and_b32_e32 v139, 0xffff0000, v139
	v_add_f32_e32 v138, v142, v138
	v_add_f32_e32 v139, v143, v139
	v_cndmask_b32_e32 v2, v2, v4, vcc
	v_div_scale_f32 v3, s[6:7], v2, v2, 1.0
	v_rcp_f32_e32 v4, v3
	v_mov_b32_e32 v176, v173
	v_mov_b32_e32 v177, v145
	v_mov_b32_e32 v142, v172
	v_fma_f32 v5, -v3, v4, 1.0
	v_fmac_f32_e32 v4, v5, v4
	v_div_scale_f32 v5, vcc, 1.0, v2, 1.0
	v_mul_f32_e32 v12, v5, v4
	v_fma_f32 v13, -v3, v12, v5
	v_mov_b32_e32 v143, v144
	v_mul_f32_e32 v176, v176, v176
	v_mul_f32_e32 v177, v177, v177
	v_mov_b32_e32 v178, v147
	v_mov_b32_e32 v179, v139
	v_fmac_f32_e32 v12, v13, v4
	v_fma_f32 v142, v142, v142, v176
	v_fma_f32 v143, v143, v143, v177
	v_mov_b32_e32 v176, v146
	v_mov_b32_e32 v177, v138
	v_mul_f32_e32 v178, v178, v178
	v_mul_f32_e32 v179, v179, v179
	v_fma_f32 v3, -v3, v12, v5
	v_fma_f32 v176, v176, v176, v178
	v_fma_f32 v177, v177, v177, v179
	s_lshl_b64 s[16:17], s[10:11], 11
	v_div_fmas_f32 v3, v3, v4, v12
	v_add_f32_e32 v142, v142, v176
	v_add_f32_e32 v143, v143, v177
	s_waitcnt lgkmcnt(0)
	s_barrier
	v_div_fixup_f32 v168, v3, v2, 1.0
	v_lshl_add_u64 v[2:3], s[16:17], 1, v[34:35]
	v_lshl_add_u32 v166, v166, 4, 0
	v_add_f32_e32 v176, v142, v143
	v_add_f32_e32 v177, v143, v142
	s_waitcnt vmcnt(41)
	v_lshlrev_b32_e32 v142, 16, v128
	v_and_b32_e32 v143, 0xffff0000, v128
	s_waitcnt vmcnt(40)
	v_lshlrev_b32_e32 v178, 16, v126
	v_and_b32_e32 v179, 0xffff0000, v126
	v_lshlrev_b32_e32 v128, 16, v129
	v_and_b32_e32 v129, 0xffff0000, v129
	v_lshlrev_b32_e32 v126, 16, v127
	v_and_b32_e32 v127, 0xffff0000, v127
	v_lshl_add_u64 v[170:171], v[2:3], 0, v[0:1]
	ds_read_b128 v[2:5], v166
	v_add_f32_e32 v142, v142, v178
	v_add_f32_e32 v143, v143, v179
	v_add_f32_e32 v178, v128, v126
	v_add_f32_e32 v179, v129, v127
	v_mov_b32_e32 v128, v143
	v_mov_b32_e32 v129, v179
	v_mov_b32_e32 v126, v142
	v_mov_b32_e32 v127, v178
	v_mul_f32_e32 v128, v128, v128
	v_mul_f32_e32 v129, v129, v129
	v_lshlrev_b32_e32 v12, 16, v8
	v_and_b32_e32 v13, 0xffff0000, v8
	v_lshlrev_b32_e32 v16, 16, v9
	v_and_b32_e32 v17, 0xffff0000, v9
	v_mul_f32_e32 v24, v6, v168
	v_mul_f32_e32 v25, v7, v168
	ds_read_b128 v[6:9], v166 offset:1024
	v_fma_f32 v126, v126, v126, v128
	v_fma_f32 v127, v127, v127, v129
	s_waitcnt vmcnt(38)
	v_lshlrev_b32_e32 v128, 16, v120
	v_and_b32_e32 v129, 0xffff0000, v120
	s_waitcnt vmcnt(37)
	v_lshlrev_b32_e32 v180, 16, v118
	v_and_b32_e32 v181, 0xffff0000, v118
	v_lshlrev_b32_e32 v120, 16, v121
	v_and_b32_e32 v121, 0xffff0000, v121
	v_lshlrev_b32_e32 v118, 16, v119
	v_and_b32_e32 v119, 0xffff0000, v119
	v_mul_f32_e32 v20, v154, v168
	v_mul_f32_e32 v21, v155, v168
	v_add_f32_e32 v128, v128, v180
	v_add_f32_e32 v129, v129, v181
	v_add_f32_e32 v118, v120, v118
	v_add_f32_e32 v119, v121, v119
	s_waitcnt vmcnt(35)
	v_lshlrev_b32_e32 v184, 16, v108
	v_and_b32_e32 v185, 0xffff0000, v108
	s_waitcnt vmcnt(34)
	v_lshlrev_b32_e32 v186, 16, v106
	v_and_b32_e32 v187, 0xffff0000, v106
	v_lshlrev_b32_e32 v108, 16, v109
	v_and_b32_e32 v109, 0xffff0000, v109
	v_lshlrev_b32_e32 v106, 16, v107
	v_and_b32_e32 v107, 0xffff0000, v107
	s_waitcnt lgkmcnt(1)
	v_mul_f32_e32 v24, v2, v24
	v_mul_f32_e32 v25, v3, v25
	v_mul_f32_e32 v20, v4, v20
	v_mul_f32_e32 v21, v5, v21
	v_mul_f32_e32 v120, v129, v129
	v_mul_f32_e32 v180, v119, v119
	v_add_f32_e32 v186, v184, v186
	v_add_f32_e32 v187, v185, v187
	v_add_f32_e32 v106, v108, v106
	v_add_f32_e32 v107, v109, v107
	v_mul_f32_e32 v16, v20, v16
	v_mul_f32_e32 v17, v21, v17
	v_mul_f32_e32 v12, v24, v12
	v_mul_f32_e32 v13, v25, v13
	v_pk_add_f32 v[126:127], v[126:127], v[126:127] op_sel:[0,1] op_sel_hi:[1,0]
	v_fma_f32 v121, v129, v129, v120
	v_fma_f32 v120, v128, v128, v120
	v_fma_f32 v181, v119, v119, v180
	v_fma_f32 v180, v118, v118, v180
	v_mul_f32_e32 v108, v186, v186
	v_mul_f32_e32 v109, v187, v187
	v_mul_f32_e32 v184, v106, v106
	v_mul_f32_e32 v185, v107, v107
	v_cvt_pk_bf16_f32 v12, v12, v13
	v_cvt_pk_bf16_f32 v13, v16, v17
	v_mul_f32_e32 v16, v150, v168
	v_mul_f32_e32 v17, v151, v168
	v_mul_f32_e32 v20, v100, v168
	v_mul_f32_e32 v21, v101, v168
	v_mov_b32_e32 v177, v108
	v_mov_b32_e32 v127, v109
	v_mov_b32_e32 v121, v184
	v_mov_b32_e32 v181, v185
	global_store_dwordx2 v[170:171], v[12:13], off
	v_lshlrev_b32_e32 v12, 16, v10
	v_and_b32_e32 v13, 0xffff0000, v10
	v_lshlrev_b32_e32 v10, 16, v11
	v_and_b32_e32 v11, 0xffff0000, v11
	s_waitcnt lgkmcnt(0)
	v_mul_f32_e32 v20, v6, v20
	v_mul_f32_e32 v21, v7, v21
	v_mul_f32_e32 v16, v8, v16
	v_mul_f32_e32 v17, v9, v17
	v_add_f32_e32 v108, v176, v126
	v_add_f32_e32 v109, v177, v127
	v_add_f32_e32 v120, v120, v180
	v_add_f32_e32 v121, v121, v181
	v_mul_f32_e32 v10, v16, v10
	v_mul_f32_e32 v11, v17, v11
	v_mul_f32_e32 v12, v20, v12
	v_mul_f32_e32 v13, v21, v13
	v_add_f32_e32 v108, v108, v120
	v_add_f32_e32 v109, v109, v121
	s_waitcnt vmcnt(33)
	v_lshlrev_b32_e32 v120, 16, v98
	v_and_b32_e32 v121, 0xffff0000, v98
	s_waitcnt vmcnt(32)
	v_lshlrev_b32_e32 v126, 16, v96
	v_and_b32_e32 v127, 0xffff0000, v96
	v_lshlrev_b32_e32 v98, 16, v99
	v_and_b32_e32 v99, 0xffff0000, v99
	v_lshlrev_b32_e32 v96, 16, v97
	v_and_b32_e32 v97, 0xffff0000, v97
	v_cvt_pk_bf16_f32 v12, v12, v13
	v_cvt_pk_bf16_f32 v13, v10, v11
	v_add_f32_e32 v120, v120, v126
	v_add_f32_e32 v121, v121, v127
	v_add_f32_e32 v96, v98, v96
	v_add_f32_e32 v97, v99, v97
	global_store_dwordx2 v[170:171], v[12:13], off offset:512
	ds_read_b128 v[10:13], v166 offset:2048
	v_mov_b32_e32 v126, v121
	v_mov_b32_e32 v127, v97
	v_mov_b32_e32 v98, v120
	v_mov_b32_e32 v99, v96
	v_mul_f32_e32 v126, v126, v126
	v_mul_f32_e32 v127, v127, v127
	s_waitcnt vmcnt(30)
	v_lshlrev_b32_e32 v176, 16, v82
	v_fma_f32 v98, v98, v98, v126
	v_fma_f32 v99, v99, v99, v127
	v_lshlrev_b32_e32 v126, 16, v84
	v_and_b32_e32 v127, 0xffff0000, v84
	v_and_b32_e32 v177, 0xffff0000, v82
	v_lshlrev_b32_e32 v84, 16, v85
	v_and_b32_e32 v85, 0xffff0000, v85
	v_lshlrev_b32_e32 v82, 16, v83
	v_and_b32_e32 v83, 0xffff0000, v83
	v_lshlrev_b32_e32 v20, 16, v14
	v_and_b32_e32 v21, 0xffff0000, v14
	v_lshlrev_b32_e32 v24, 16, v15
	v_and_b32_e32 v25, 0xffff0000, v15
	ds_read_b128 v[14:17], v166 offset:3072
	v_add_f32_e32 v176, v126, v176
	v_add_f32_e32 v177, v127, v177
	v_add_f32_e32 v82, v84, v82
	v_add_f32_e32 v83, v85, v83
	s_waitcnt vmcnt(28)
	v_lshlrev_b32_e32 v180, 16, v78
	v_and_b32_e32 v181, 0xffff0000, v78
	s_waitcnt vmcnt(27)
	v_lshlrev_b32_e32 v184, 16, v74
	v_and_b32_e32 v185, 0xffff0000, v74
	v_lshlrev_b32_e32 v78, 16, v79
	v_and_b32_e32 v79, 0xffff0000, v79
	v_lshlrev_b32_e32 v74, 16, v75
	v_and_b32_e32 v75, 0xffff0000, v75
	v_mul_f32_e32 v100, v156, v168
	v_mul_f32_e32 v101, v157, v168
	v_mul_f32_e32 v150, v152, v168
	v_mul_f32_e32 v151, v153, v168
	v_mul_f32_e32 v84, v177, v177
	v_mul_f32_e32 v126, v83, v83
	v_add_f32_e32 v180, v180, v184
	v_add_f32_e32 v181, v181, v185
	v_add_f32_e32 v78, v78, v74
	v_add_f32_e32 v79, v79, v75
	s_waitcnt lgkmcnt(1)
	v_mul_f32_e32 v150, v10, v150
	v_mul_f32_e32 v151, v11, v151
	v_mul_f32_e32 v100, v12, v100
	v_mul_f32_e32 v101, v13, v101
	v_pk_add_f32 v[108:109], v[108:109], v[108:109] op_sel:[0,1] op_sel_hi:[1,0]
	v_pk_add_f32 v[98:99], v[98:99], v[98:99] op_sel:[0,1] op_sel_hi:[1,0]
	v_fma_f32 v85, v177, v177, v84
	v_fma_f32 v84, v176, v176, v84
	v_fma_f32 v127, v83, v83, v126
	v_fma_f32 v126, v82, v82, v126
	v_mul_f32_e32 v74, v180, v180
	v_mul_f32_e32 v75, v181, v181
	v_mul_f32_e32 v184, v78, v78
	v_mul_f32_e32 v185, v79, v79
	v_mul_f32_e32 v24, v100, v24
	v_mul_f32_e32 v25, v101, v25
	v_mul_f32_e32 v20, v150, v20
	v_mul_f32_e32 v21, v151, v21
	v_mov_b32_e32 v109, v74
	v_mov_b32_e32 v99, v75
	v_mov_b32_e32 v85, v184
	v_mov_b32_e32 v127, v185
	v_cvt_pk_bf16_f32 v20, v20, v21
	v_cvt_pk_bf16_f32 v21, v24, v25
	v_mul_f32_e32 v24, v148, v168
	v_mul_f32_e32 v25, v149, v168
	v_mul_f32_e32 v100, v140, v168
	v_mul_f32_e32 v101, v141, v168
	v_add_f32_e32 v74, v108, v98
	v_add_f32_e32 v75, v109, v99
	v_add_f32_e32 v84, v84, v126
	v_add_f32_e32 v85, v85, v127
	global_store_dwordx2 v[170:171], v[20:21], off offset:1024
	v_lshlrev_b32_e32 v20, 16, v18
	v_and_b32_e32 v21, 0xffff0000, v18
	v_lshlrev_b32_e32 v18, 16, v19
	v_and_b32_e32 v19, 0xffff0000, v19
	s_waitcnt lgkmcnt(0)
; #define GAS __attribute__((address_space(1)))
; #define LAS __attribute__((address_space(3)))
; template <bool HG>
; __device__ __forceinline__ void readout_phase2(const Args& a, Frame& F, const float* gain, int nrows) {
;     ...
;     RO_LOAD(f0, b0, g0, nw); RO_LOAD(f1, b1, g1, nw + 2048); RO_LOAD(f2, b2, g2, nw + 2 * 2048);
;     if (HG) { for (int q = F.tid; q < D / 4; q += NWAVES * 64) ((LAS f32x4*)GL)[q] = ((const GAS f32x4*)gain)[q];
;               asm volatile("s_waitcnt lgkmcnt(0)" ::: "memory"); __builtin_amdgcn_s_barrier(); asm volatile("" ::: "memory"); }
;     RO_FINISH(f0, b0, g0, nw);            RO_LOAD(f0, b0, g0, nw + 3 * 2048);
;     RO_FINISH(f1, b1, g1, nw + 2048);     RO_LOAD(f1, b1, g1, nw + 4 * 2048);
	v_mul_f32_e32 v100, v14, v100
	v_mul_f32_e32 v101, v15, v101
	v_mul_f32_e32 v24, v16, v24
	v_mul_f32_e32 v25, v17, v25
	v_add_f32_e32 v74, v74, v84
	v_add_f32_e32 v75, v75, v85
	v_mul_f32_e32 v18, v24, v18
	v_mul_f32_e32 v19, v25, v19
	v_mul_f32_e32 v20, v100, v20
	v_mul_f32_e32 v21, v101, v21
	v_add_f32_e32 v74, v74, v75
	v_cvt_pk_bf16_f32 v20, v20, v21
	v_cvt_pk_bf16_f32 v21, v18, v19
	v_add_f32_dpp v74, v74, v74 quad_perm:[1,0,3,2] row_mask:0xf bank_mask:0xf bound_ctrl:1
	global_store_dwordx2 v[170:171], v[20:21], off offset:1536
	ds_read_b128 v[18:21], v166 offset:4096
	v_add_f32_dpp v74, v74, v74 quad_perm:[2,3,0,1] row_mask:0xf bank_mask:0xf bound_ctrl:1
	v_lshlrev_b32_e32 v100, 16, v22
	v_and_b32_e32 v101, 0xffff0000, v22
	v_add_f32_dpp v74, v74, v74 row_half_mirror row_mask:0xf bank_mask:0xf bound_ctrl:1
	v_lshlrev_b32_e32 v140, 16, v23
	v_and_b32_e32 v141, 0xffff0000, v23
	v_add_f32_dpp v74, v74, v74 row_mirror row_mask:0xf bank_mask:0xf bound_ctrl:1
	ds_read_b128 v[22:25], v166 offset:5120
	v_readlane_b32 s8, v74, 16
	v_readlane_b32 s9, v74, 48
	v_mul_f32_e32 v148, v158, v168
	v_mul_f32_e32 v149, v159, v168
	v_mul_f32_e32 v80, v80, v168
	v_mul_f32_e32 v81, v81, v168
	v_readlane_b32 s6, v74, 0
	v_readlane_b32 s7, v74, 32
	v_mov_b32_e32 v74, s8
	v_mov_b32_e32 v75, s9
	s_waitcnt lgkmcnt(1)
	v_mul_f32_e32 v80, v18, v80
	v_mul_f32_e32 v81, v19, v81
	v_mul_f32_e32 v148, v20, v148
	v_mul_f32_e32 v149, v21, v149
	v_add_f32_e32 v74, s6, v74
	v_add_f32_e32 v75, s7, v75
	v_mul_f32_e32 v140, v148, v140
	v_mul_f32_e32 v141, v149, v141
	v_mul_f32_e32 v80, v80, v100
	v_mul_f32_e32 v81, v81, v101
	v_add_f32_e32 v74, v74, v75
	v_cvt_pk_bf16_f32 v80, v80, v81
	v_cvt_pk_bf16_f32 v81, v140, v141
	v_mul_f32_e32 v28, v28, v168
	v_mul_f32_e32 v29, v29, v168
	v_mul_f32_e32 v32, v32, v168
	v_mul_f32_e32 v33, v33, v168
	v_fmamk_f32 v74, v74, 0x3a000000, v252
	global_store_dwordx2 v[170:171], v[80:81], off offset:2048
	v_lshlrev_b32_e32 v80, 16, v26
	v_and_b32_e32 v81, 0xffff0000, v26
	v_lshlrev_b32_e32 v26, 16, v27
	v_and_b32_e32 v27, 0xffff0000, v27
	s_waitcnt lgkmcnt(0)
	v_mul_f32_e32 v32, v32, v22
	v_mul_f32_e32 v33, v33, v23
	v_mul_f32_e32 v28, v28, v24
	v_mul_f32_e32 v29, v29, v25
	v_mul_f32_e32 v75, 0x4f800000, v74
	v_cmp_gt_f32_e32 vcc, s55, v74
	v_mul_f32_e32 v26, v28, v26
	v_mul_f32_e32 v27, v29, v27
	v_mul_f32_e32 v28, v32, v80
	v_mul_f32_e32 v29, v33, v81
	v_cndmask_b32_e32 v74, v74, v75, vcc
	v_cvt_pk_bf16_f32 v28, v28, v29
	v_cvt_pk_bf16_f32 v29, v26, v27
	v_sqrt_f32_e32 v75, v74
	global_store_dwordx2 v[170:171], v[28:29], off offset:2560
	ds_read_b128 v[26:29], v166 offset:6144
	v_lshlrev_b32_e32 v80, 16, v30
	v_and_b32_e32 v81, 0xffff0000, v30
	v_lshlrev_b32_e32 v100, 16, v31
	v_and_b32_e32 v101, 0xffff0000, v31
	ds_read_b128 v[30:33], v166 offset:7168
	v_add_u32_e32 v84, -1, v75
	v_mul_f32_e32 v140, v164, v168
	v_mul_f32_e32 v141, v165, v168
	v_mul_f32_e32 v148, v160, v168
	v_mul_f32_e32 v149, v161, v168
	v_fma_f32 v85, -v84, v75, v74
	s_waitcnt lgkmcnt(1)
	v_mul_f32_e32 v148, v148, v26
	v_mul_f32_e32 v149, v149, v27
	v_mul_f32_e32 v140, v140, v28
	v_mul_f32_e32 v141, v141, v29
	v_cmp_ge_f32_e64 s[8:9], 0, v85
	v_add_u32_e32 v85, 1, v75
	v_mul_f32_e32 v100, v140, v100
	v_mul_f32_e32 v101, v141, v101
	v_mul_f32_e32 v80, v148, v80
	v_mul_f32_e32 v81, v149, v81
	v_cndmask_b32_e64 v84, v75, v84, s[8:9]
	v_fma_f32 v75, -v85, v75, v74
	s_lshl_b64 s[14:15], s[12:13], 11
	v_cvt_pk_bf16_f32 v80, v80, v81
	v_cvt_pk_bf16_f32 v81, v100, v101
	v_mul_f32_e32 v100, v162, v168
	v_mul_f32_e32 v101, v163, v168
	v_mul_f32_e32 v90, v90, v168
	v_mul_f32_e32 v91, v91, v168
	s_lshl_b64 s[12:13], s[10:11], 12
	v_cmp_lt_f32_e64 s[8:9], 0, v75
	global_store_dwordx2 v[170:171], v[80:81], off offset:3072
	v_lshlrev_b32_e32 v80, 16, v76
	v_and_b32_e32 v81, 0xffff0000, v76
	v_lshlrev_b32_e32 v76, 16, v77
	v_and_b32_e32 v77, 0xffff0000, v77
	s_waitcnt lgkmcnt(0)
	v_mul_f32_e32 v90, v90, v30
	v_mul_f32_e32 v91, v91, v31
	v_mul_f32_e32 v100, v100, v32
	v_mul_f32_e32 v101, v101, v33
	s_add_u32 s16, s12, 0x1800000
	v_cndmask_b32_e64 v75, v84, v85, s[8:9]
	v_mul_f32_e32 v76, v100, v76
	v_mul_f32_e32 v77, v101, v77
	v_mul_f32_e32 v80, v90, v80
	v_mul_f32_e32 v81, v91, v81
	s_addc_u32 s17, s13, 0
	v_mul_f32_e32 v84, 0x37800000, v75
	v_cvt_pk_bf16_f32 v80, v80, v81
	v_cvt_pk_bf16_f32 v81, v76, v77
	v_lshl_add_u64 v[76:77], v[36:37], 0, s[16:17]
	v_cndmask_b32_e32 v75, v75, v84, vcc
	v_cmp_class_f32_e32 vcc, v74, v253
	v_lshl_add_u64 v[140:141], v[76:77], 0, v[0:1]
	v_lshl_add_u64 v[76:77], v[38:39], 0, s[16:17]
	v_cndmask_b32_e32 v84, v75, v74, vcc
	global_store_dwordx2 v[170:171], v[80:81], off offset:3584
	v_lshl_add_u64 v[170:171], v[76:77], 0, v[0:1]
	v_lshl_add_u64 v[76:77], v[40:41], 0, s[16:17]
	v_div_scale_f32 v85, s[6:7], v84, v84, 1.0
	v_lshl_add_u64 v[166:167], v[76:77], 0, v[0:1]
	global_load_dwordx2 v[168:169], v[140:141], off nt
	global_load_dwordx2 v[162:163], v[140:141], off offset:512 nt
	global_load_dwordx2 v[158:159], v[140:141], off offset:1024 nt
	global_load_dwordx2 v[154:155], v[140:141], off offset:1536 nt
	global_load_dwordx2 v[174:175], v[170:171], off nt
	global_load_dwordx2 v[164:165], v[170:171], off offset:512 nt
	global_load_dwordx2 v[160:161], v[170:171], off offset:1024 nt
	global_load_dwordx2 v[156:157], v[170:171], off offset:1536 nt
	global_load_dwordx2 v[100:101], v[166:167], off nt
	global_load_dwordx2 v[90:91], v[166:167], off offset:512 nt
	global_load_dwordx2 v[80:81], v[166:167], off offset:1024 nt
	global_load_dwordx2 v[76:77], v[166:167], off offset:1536 nt
	global_load_dwordx2 v[152:153], v[140:141], off offset:2048 nt
; #define GAS __attribute__((address_space(1)))
; #define LAS __attribute__((address_space(3)))
; template <bool HG>
; __device__ __forceinline__ void readout_phase2(const Args& a, Frame& F, const float* gain, int nrows) {
;     ...
;     RO_LOAD(f0, b0, g0, nw); RO_LOAD(f1, b1, g1, nw + 2048); RO_LOAD(f2, b2, g2, nw + 2 * 2048);
;     if (HG) { for (int q = F.tid; q < D / 4; q += NWAVES * 64) ((LAS f32x4*)GL)[q] = ((const GAS f32x4*)gain)[q];
;               asm volatile("s_waitcnt lgkmcnt(0)" ::: "memory"); __builtin_amdgcn_s_barrier(); asm volatile("" ::: "memory"); }
;     RO_FINISH(f0, b0, g0, nw);            RO_LOAD(f0, b0, g0, nw + 3 * 2048);
;     RO_FINISH(f1, b1, g1, nw + 2048);     RO_LOAD(f1, b1, g1, nw + 4 * 2048);
	global_load_dwordx2 v[150:151], v[140:141], off offset:2560 nt
	global_load_dwordx2 v[148:149], v[140:141], off offset:3072 nt
	s_nop 0
	global_load_dwordx2 v[140:141], v[140:141], off offset:3584 nt
	s_nop 0
	global_load_dwordx2 v[196:197], v[170:171], off offset:2048 nt
	global_load_dwordx2 v[192:193], v[170:171], off offset:2560 nt
	global_load_dwordx2 v[188:189], v[170:171], off offset:3072 nt
	global_load_dwordx2 v[184:185], v[170:171], off offset:3584 nt
	v_rcp_f32_e32 v170, v85
	global_load_dwordx2 v[126:127], v[166:167], off offset:2048 nt
	global_load_dwordx2 v[108:109], v[166:167], off offset:2560 nt
	global_load_dwordx2 v[98:99], v[166:167], off offset:3072 nt
	global_load_dwordx2 v[74:75], v[166:167], off offset:3584 nt
	v_fma_f32 v166, -v85, v170, 1.0
	v_fmac_f32_e32 v170, v166, v170
	v_div_scale_f32 v166, vcc, 1.0, v84, 1.0
	v_mul_f32_e32 v167, v166, v170
	v_fma_f32 v171, -v85, v167, v166
	v_fmac_f32_e32 v167, v171, v170
	v_fma_f32 v85, -v85, v167, v166
	v_div_fmas_f32 v85, v85, v170, v167
	v_div_fixup_f32 v84, v85, v84, 1.0
	v_mul_f32_e32 v146, v146, v84
	v_mul_f32_e32 v147, v147, v84
	v_mul_f32_e32 v172, v172, v84
	v_mul_f32_e32 v173, v173, v84
	v_lshlrev_b32_e32 v170, 16, v72
	v_and_b32_e32 v171, 0xffff0000, v72
	v_lshlrev_b32_e32 v72, 16, v73
	v_and_b32_e32 v73, 0xffff0000, v73
	v_mul_f32_e32 v172, v2, v172
	v_mul_f32_e32 v173, v3, v173
	v_mul_f32_e32 v146, v4, v146
	v_mul_f32_e32 v147, v5, v147
	v_mul_f32_e32 v138, v138, v84
	v_mul_f32_e32 v139, v139, v84
	v_mul_f32_e32 v72, v146, v72
	v_mul_f32_e32 v73, v147, v73
	v_mul_f32_e32 v146, v172, v170
	v_mul_f32_e32 v147, v173, v171
	v_mul_f32_e32 v144, v144, v84
	v_mul_f32_e32 v145, v145, v84
	v_cvt_pk_bf16_f32 v146, v146, v147
	v_cvt_pk_bf16_f32 v147, v72, v73
	v_lshlrev_b32_e32 v72, 16, v70
	v_and_b32_e32 v73, 0xffff0000, v70
	v_lshlrev_b32_e32 v70, 16, v71
	v_and_b32_e32 v71, 0xffff0000, v71
	v_mul_f32_e32 v144, v6, v144
	v_mul_f32_e32 v145, v7, v145
	v_mul_f32_e32 v138, v8, v138
	v_mul_f32_e32 v139, v9, v139
	v_lshl_add_u64 v[166:167], s[18:19], 1, v[34:35]
	v_mul_f32_e32 v70, v138, v70
	v_mul_f32_e32 v71, v139, v71
	v_mul_f32_e32 v72, v144, v72
	v_mul_f32_e32 v73, v145, v73
	v_lshl_add_u64 v[166:167], v[166:167], 0, v[0:1]
	v_cvt_pk_bf16_f32 v72, v72, v73
	v_cvt_pk_bf16_f32 v73, v70, v71
	global_store_dwordx2 v[166:167], v[72:73], off offset:512
	v_mul_f32_e32 v72, v178, v84
	v_mul_f32_e32 v73, v179, v84
	v_mul_f32_e32 v138, v142, v84
	v_mul_f32_e32 v139, v143, v84
	v_lshlrev_b32_e32 v70, 16, v66
	v_and_b32_e32 v71, 0xffff0000, v66
	v_lshlrev_b32_e32 v66, 16, v67
	v_and_b32_e32 v67, 0xffff0000, v67
	v_mul_f32_e32 v138, v10, v138
	v_mul_f32_e32 v139, v11, v139
	v_mul_f32_e32 v72, v12, v72
	v_mul_f32_e32 v73, v13, v73
	v_mul_f32_e32 v70, v138, v70
	v_mul_f32_e32 v71, v139, v71
	v_mul_f32_e32 v66, v72, v66
	v_mul_f32_e32 v67, v73, v67
	v_cvt_pk_bf16_f32 v70, v70, v71
	v_cvt_pk_bf16_f32 v71, v66, v67
	global_store_dwordx2 v[166:167], v[70:71], off offset:1024
	v_mul_f32_e32 v70, v118, v84
	v_mul_f32_e32 v71, v119, v84
	v_mul_f32_e32 v72, v128, v84
	v_mul_f32_e32 v73, v129, v84
	v_lshlrev_b32_e32 v66, 16, v60
	v_and_b32_e32 v67, 0xffff0000, v60
	v_lshlrev_b32_e32 v60, 16, v61
	v_and_b32_e32 v61, 0xffff0000, v61
	v_mul_f32_e32 v72, v14, v72
	v_mul_f32_e32 v73, v15, v73
	v_mul_f32_e32 v70, v16, v70
	v_mul_f32_e32 v71, v17, v71
	v_mul_f32_e32 v66, v72, v66
	v_mul_f32_e32 v67, v73, v67
	v_mul_f32_e32 v60, v70, v60
	v_mul_f32_e32 v61, v71, v61
	v_cvt_pk_bf16_f32 v66, v66, v67
	v_cvt_pk_bf16_f32 v67, v60, v61
	global_store_dwordx2 v[166:167], v[66:67], off offset:1536
	v_mul_f32_e32 v66, v106, v84
	v_mul_f32_e32 v67, v107, v84
	v_mul_f32_e32 v70, v186, v84
	v_mul_f32_e32 v71, v187, v84
	v_lshlrev_b32_e32 v60, 16, v54
	v_and_b32_e32 v61, 0xffff0000, v54
	v_lshlrev_b32_e32 v54, 16, v55
	v_and_b32_e32 v55, 0xffff0000, v55
	v_mul_f32_e32 v70, v18, v70
	v_mul_f32_e32 v71, v19, v71
	v_mul_f32_e32 v66, v20, v66
	v_mul_f32_e32 v67, v21, v67
	v_mul_f32_e32 v60, v70, v60
	v_mul_f32_e32 v61, v71, v61
	v_mul_f32_e32 v54, v66, v54
	v_mul_f32_e32 v55, v67, v55
	v_cvt_pk_bf16_f32 v60, v60, v61
	v_cvt_pk_bf16_f32 v61, v54, v55
	global_store_dwordx2 v[166:167], v[60:61], off offset:2048
	v_mul_f32_e32 v60, v96, v84
	v_mul_f32_e32 v61, v97, v84
	v_mul_f32_e32 v66, v120, v84
	v_mul_f32_e32 v67, v121, v84
	v_lshlrev_b32_e32 v54, 16, v46
	v_and_b32_e32 v55, 0xffff0000, v46
	v_lshlrev_b32_e32 v46, 16, v47
	v_and_b32_e32 v47, 0xffff0000, v47
	v_mul_f32_e32 v66, v22, v66
	v_mul_f32_e32 v67, v23, v67
	v_mul_f32_e32 v60, v24, v60
	v_mul_f32_e32 v61, v25, v61
	v_mul_f32_e32 v54, v66, v54
	v_mul_f32_e32 v55, v67, v55
	v_mul_f32_e32 v46, v60, v46
	v_mul_f32_e32 v47, v61, v47
	v_cvt_pk_bf16_f32 v54, v54, v55
	v_cvt_pk_bf16_f32 v55, v46, v47
	global_store_dwordx2 v[166:167], v[54:55], off offset:2560
	v_mul_f32_e32 v54, v82, v84
	v_mul_f32_e32 v55, v83, v84
	v_mul_f32_e32 v60, v176, v84
	v_mul_f32_e32 v61, v177, v84
	v_lshlrev_b32_e32 v46, 16, v44
	v_and_b32_e32 v47, 0xffff0000, v44
	v_lshlrev_b32_e32 v44, 16, v45
	v_and_b32_e32 v45, 0xffff0000, v45
	v_mul_f32_e32 v60, v26, v60
	v_mul_f32_e32 v61, v27, v61
	v_mul_f32_e32 v54, v28, v54
	v_mul_f32_e32 v55, v29, v55
	v_mul_f32_e32 v46, v60, v46
	v_mul_f32_e32 v47, v61, v47
	v_mul_f32_e32 v44, v54, v44
	v_mul_f32_e32 v45, v55, v45
	v_cvt_pk_bf16_f32 v46, v46, v47
	v_cvt_pk_bf16_f32 v47, v44, v45
	global_store_dwordx2 v[166:167], v[46:47], off offset:3072
	v_mul_f32_e32 v46, v78, v84
	v_mul_f32_e32 v47, v79, v84
	v_mul_f32_e32 v54, v180, v84
	v_mul_f32_e32 v55, v181, v84
	s_waitcnt vmcnt(62)
; #define GAS __attribute__((address_space(1)))
; #define LAS __attribute__((address_space(3)))
; template <bool HG>
; __device__ __forceinline__ void readout_phase2(const Args& a, Frame& F, const float* gain, int nrows) {
;     ...
;     RO_LOAD(f0, b0, g0, nw); RO_LOAD(f1, b1, g1, nw + 2048); RO_LOAD(f2, b2, g2, nw + 2 * 2048);
;     if (HG) { for (int q = F.tid; q < D / 4; q += NWAVES * 64) ((LAS f32x4*)GL)[q] = ((const GAS f32x4*)gain)[q];
;               asm volatile("s_waitcnt lgkmcnt(0)" ::: "memory"); __builtin_amdgcn_s_barrier(); asm volatile("" ::: "memory"); }
;     RO_FINISH(f0, b0, g0, nw);            RO_LOAD(f0, b0, g0, nw + 3 * 2048);
;     RO_FINISH(f1, b1, g1, nw + 2048);     RO_LOAD(f1, b1, g1, nw + 4 * 2048);
;     RO_FINISH(f2, b2, g2, nw + 2 * 2048); RO_LOAD(f2, b2, g2, nw + 5 * 2048);
	v_lshlrev_b32_e32 v44, 16, v42
	v_and_b32_e32 v45, 0xffff0000, v42
	v_lshlrev_b32_e32 v42, 16, v43
	v_and_b32_e32 v43, 0xffff0000, v43
	v_mul_f32_e32 v54, v30, v54
	v_mul_f32_e32 v55, v31, v55
	v_mul_f32_e32 v46, v32, v46
	v_mul_f32_e32 v47, v33, v47
	s_add_u32 s18, s12, 0x2000000
	v_mul_f32_e32 v42, v46, v42
	v_mul_f32_e32 v43, v47, v43
	v_mul_f32_e32 v44, v54, v44
	v_mul_f32_e32 v45, v55, v45
	s_addc_u32 s19, s13, 0
	v_cvt_pk_bf16_f32 v44, v44, v45
	v_cvt_pk_bf16_f32 v45, v42, v43
	v_lshl_add_u64 v[42:43], v[36:37], 0, s[18:19]
	v_lshl_add_u64 v[70:71], v[42:43], 0, v[0:1]
	v_lshl_add_u64 v[42:43], v[38:39], 0, s[18:19]
	global_store_dwordx2 v[166:167], v[146:147], off
	global_store_dwordx2 v[166:167], v[44:45], off offset:3584
	v_lshl_add_u64 v[44:45], v[42:43], 0, v[0:1]
	v_lshl_add_u64 v[42:43], v[40:41], 0, s[18:19]
	v_lshl_add_u64 v[42:43], v[42:43], 0, v[0:1]
	global_load_dwordx2 v[170:171], v[70:71], off nt
	global_load_dwordx2 v[144:145], v[70:71], off offset:512 nt
	global_load_dwordx2 v[138:139], v[70:71], off offset:1024 nt
	global_load_dwordx2 v[118:119], v[70:71], off offset:1536 nt
	global_load_dwordx2 v[176:177], v[44:45], off nt
	global_load_dwordx2 v[146:147], v[44:45], off offset:512 nt
	global_load_dwordx2 v[142:143], v[44:45], off offset:1024 nt
	global_load_dwordx2 v[120:121], v[44:45], off offset:1536 nt
	global_load_dwordx2 v[66:67], v[42:43], off nt
	global_load_dwordx2 v[60:61], v[42:43], off offset:512 nt
	global_load_dwordx2 v[54:55], v[42:43], off offset:1024 nt
	global_load_dwordx2 v[46:47], v[42:43], off offset:1536 nt
	global_load_dwordx2 v[106:107], v[70:71], off offset:2048 nt
	global_load_dwordx2 v[96:97], v[70:71], off offset:2560 nt
	global_load_dwordx2 v[82:83], v[70:71], off offset:3072 nt
	global_load_dwordx2 v[72:73], v[70:71], off offset:3584 nt
	s_waitcnt vmcnt(62)
	v_lshlrev_b32_e32 v70, 16, v136
	v_and_b32_e32 v71, 0xffff0000, v136
	v_lshlrev_b32_e32 v78, 16, v134
	v_and_b32_e32 v79, 0xffff0000, v134
	v_add_f32_e32 v78, v70, v78
	v_add_f32_e32 v79, v71, v79
	v_lshlrev_b32_e32 v70, 16, v137
	v_and_b32_e32 v71, 0xffff0000, v137
	v_lshlrev_b32_e32 v84, 16, v135
	v_and_b32_e32 v85, 0xffff0000, v135
	v_add_f32_e32 v128, v70, v84
	v_add_f32_e32 v129, v71, v85
	v_lshlrev_b32_e32 v70, 16, v132
	v_and_b32_e32 v71, 0xffff0000, v132
	v_lshlrev_b32_e32 v84, 16, v130
	v_and_b32_e32 v85, 0xffff0000, v130
	v_add_f32_e32 v70, v70, v84
	v_add_f32_e32 v71, v71, v85
	v_lshlrev_b32_e32 v84, 16, v133
	v_and_b32_e32 v85, 0xffff0000, v133
	v_lshlrev_b32_e32 v130, 16, v131
	v_and_b32_e32 v131, 0xffff0000, v131
	v_add_f32_e32 v84, v84, v130
	v_add_f32_e32 v85, v85, v131
	v_mov_b32_e32 v132, v79
	v_mov_b32_e32 v133, v71
	v_mov_b32_e32 v130, v78
	v_mov_b32_e32 v131, v70
	v_mul_f32_e32 v132, v132, v132
	v_mul_f32_e32 v133, v133, v133
	v_mov_b32_e32 v134, v129
	v_mov_b32_e32 v135, v85
	v_fma_f32 v130, v130, v130, v132
	v_fma_f32 v131, v131, v131, v133
	v_mov_b32_e32 v132, v128
	v_mov_b32_e32 v133, v84
	v_mul_f32_e32 v134, v134, v134
	v_mul_f32_e32 v135, v135, v135
	v_lshlrev_b32_e32 v136, 16, v116
	v_fma_f32 v132, v132, v132, v134
	v_fma_f32 v133, v133, v133, v135
	v_lshlrev_b32_e32 v134, 16, v122
	v_add_f32_e32 v130, v130, v132
	v_add_f32_e32 v131, v131, v133
	v_and_b32_e32 v135, 0xffff0000, v122
	v_add_f32_e32 v132, v130, v131
	v_add_f32_e32 v133, v131, v130
	v_lshlrev_b32_e32 v130, 16, v124
	v_and_b32_e32 v131, 0xffff0000, v124
	v_lshlrev_b32_e32 v124, 16, v125
	v_and_b32_e32 v125, 0xffff0000, v125
	v_lshlrev_b32_e32 v122, 16, v123
	v_and_b32_e32 v123, 0xffff0000, v123
	v_add_f32_e32 v130, v130, v134
	v_add_f32_e32 v131, v131, v135
	v_add_f32_e32 v134, v124, v122
	v_add_f32_e32 v135, v125, v123
	v_mov_b32_e32 v124, v131
	v_mov_b32_e32 v125, v135
	v_mov_b32_e32 v122, v130
	v_mov_b32_e32 v123, v134
	v_mul_f32_e32 v124, v124, v124
	v_mul_f32_e32 v125, v125, v125
	v_and_b32_e32 v137, 0xffff0000, v116
	v_fma_f32 v122, v122, v122, v124
	v_fma_f32 v123, v123, v123, v125
	v_lshlrev_b32_e32 v124, 16, v114
	v_and_b32_e32 v125, 0xffff0000, v114
	v_lshlrev_b32_e32 v114, 16, v115
	v_and_b32_e32 v115, 0xffff0000, v115
	v_lshlrev_b32_e32 v116, 16, v117
	v_and_b32_e32 v117, 0xffff0000, v117
	v_add_f32_e32 v124, v124, v136
	v_add_f32_e32 v125, v125, v137
	v_add_f32_e32 v114, v114, v116
	v_add_f32_e32 v115, v115, v117
	v_lshlrev_b32_e32 v166, 16, v112
	v_and_b32_e32 v167, 0xffff0000, v112
	v_lshlrev_b32_e32 v172, 16, v110
	v_and_b32_e32 v173, 0xffff0000, v110
	v_lshlrev_b32_e32 v112, 16, v113
	v_and_b32_e32 v113, 0xffff0000, v113
	v_lshlrev_b32_e32 v110, 16, v111
	v_and_b32_e32 v111, 0xffff0000, v111
	v_mul_f32_e32 v116, v125, v125
	v_mul_f32_e32 v136, v115, v115
	v_add_f32_e32 v166, v166, v172
	v_add_f32_e32 v167, v167, v173
	v_add_f32_e32 v112, v112, v110
	v_add_f32_e32 v113, v113, v111
	v_pk_add_f32 v[122:123], v[122:123], v[122:123] op_sel:[0,1] op_sel_hi:[1,0]
	v_fma_f32 v117, v125, v125, v116
	v_fma_f32 v116, v124, v124, v116
	v_fma_f32 v137, v115, v115, v136
	v_fma_f32 v136, v114, v114, v136
	v_mul_f32_e32 v110, v166, v166
	v_mul_f32_e32 v111, v167, v167
	v_mul_f32_e32 v172, v112, v112
	v_mul_f32_e32 v173, v113, v113
	v_mov_b32_e32 v133, v110
	v_mov_b32_e32 v123, v111
	v_mov_b32_e32 v117, v172
	v_mov_b32_e32 v137, v173
	v_add_f32_e32 v110, v132, v122
	v_add_f32_e32 v111, v133, v123
	v_add_f32_e32 v116, v116, v136
	v_add_f32_e32 v117, v117, v137
	v_lshlrev_b32_e32 v122, 16, v102
	v_add_f32_e32 v110, v110, v116
	v_add_f32_e32 v111, v111, v117
	v_lshlrev_b32_e32 v116, 16, v104
	v_and_b32_e32 v117, 0xffff0000, v104
	v_and_b32_e32 v123, 0xffff0000, v102
	v_lshlrev_b32_e32 v104, 16, v105
	v_and_b32_e32 v105, 0xffff0000, v105
	v_lshlrev_b32_e32 v102, 16, v103
	v_and_b32_e32 v103, 0xffff0000, v103
	v_add_f32_e32 v116, v116, v122
	v_add_f32_e32 v117, v117, v123
	v_add_f32_e32 v102, v104, v102
	v_add_f32_e32 v103, v105, v103
	v_mov_b32_e32 v122, v117
	v_mov_b32_e32 v123, v103
	v_mov_b32_e32 v104, v116
	v_mov_b32_e32 v105, v102
	v_mul_f32_e32 v122, v122, v122
	v_mul_f32_e32 v123, v123, v123
	s_waitcnt vmcnt(60)
	v_lshlrev_b32_e32 v132, 16, v92
	v_fma_f32 v104, v104, v104, v122
	v_fma_f32 v105, v105, v105, v123
	v_lshlrev_b32_e32 v122, 16, v94
	v_and_b32_e32 v123, 0xffff0000, v94
	v_and_b32_e32 v133, 0xffff0000, v92
	v_lshlrev_b32_e32 v94, 16, v95
	v_and_b32_e32 v95, 0xffff0000, v95
	v_lshlrev_b32_e32 v92, 16, v93
	v_and_b32_e32 v93, 0xffff0000, v93
	v_add_f32_e32 v132, v122, v132
	v_add_f32_e32 v133, v123, v133
	v_add_f32_e32 v92, v94, v92
	v_add_f32_e32 v93, v95, v93
	s_waitcnt vmcnt(58)
	v_lshlrev_b32_e32 v136, 16, v86
	v_and_b32_e32 v137, 0xffff0000, v86
	s_waitcnt vmcnt(57)
	v_lshlrev_b32_e32 v172, 16, v88
	v_and_b32_e32 v173, 0xffff0000, v88
	v_lshlrev_b32_e32 v86, 16, v87
	v_and_b32_e32 v87, 0xffff0000, v87
	v_lshlrev_b32_e32 v88, 16, v89
	v_and_b32_e32 v89, 0xffff0000, v89
	v_mul_f32_e32 v94, v133, v133
	v_mul_f32_e32 v122, v93, v93
	v_add_f32_e32 v136, v136, v172
	v_add_f32_e32 v137, v137, v173
	v_add_f32_e32 v86, v86, v88
	v_add_f32_e32 v87, v87, v89
	v_pk_add_f32 v[110:111], v[110:111], v[110:111] op_sel:[0,1] op_sel_hi:[1,0]
	v_pk_add_f32 v[104:105], v[104:105], v[104:105] op_sel:[0,1] op_sel_hi:[1,0]
	v_fma_f32 v95, v133, v133, v94
	v_fma_f32 v94, v132, v132, v94
	v_fma_f32 v123, v93, v93, v122
	v_fma_f32 v122, v92, v92, v122
	v_mul_f32_e32 v88, v136, v136
	v_mul_f32_e32 v89, v137, v137
	v_mul_f32_e32 v172, v86, v86
	v_mul_f32_e32 v173, v87, v87
	v_mov_b32_e32 v111, v88
	v_mov_b32_e32 v105, v89
	v_mov_b32_e32 v95, v172
	v_mov_b32_e32 v123, v173
	v_add_f32_e32 v88, v110, v104
	v_add_f32_e32 v89, v111, v105
	v_add_f32_e32 v94, v94, v122
	v_add_f32_e32 v95, v95, v123
	global_load_dwordx2 v[198:199], v[44:45], off offset:2048 nt
	global_load_dwordx2 v[194:195], v[44:45], off offset:2560 nt
	global_load_dwordx2 v[190:191], v[44:45], off offset:3072 nt
	global_load_dwordx2 v[186:187], v[44:45], off offset:3584 nt
	v_add_f32_e32 v88, v88, v94
	v_add_f32_e32 v89, v89, v95
	s_nop 0
	v_add_f32_e32 v88, v88, v89
	s_nop 1
	v_add_f32_dpp v88, v88, v88 quad_perm:[1,0,3,2] row_mask:0xf bank_mask:0xf bound_ctrl:1
	s_nop 1
	v_add_f32_dpp v88, v88, v88 quad_perm:[2,3,0,1] row_mask:0xf bank_mask:0xf bound_ctrl:1
	s_nop 1
	v_add_f32_dpp v88, v88, v88 row_half_mirror row_mask:0xf bank_mask:0xf bound_ctrl:1
	s_nop 1
	v_add_f32_dpp v88, v88, v88 row_mirror row_mask:0xf bank_mask:0xf bound_ctrl:1
	s_nop 0
	v_readlane_b32 s8, v88, 16
	v_readlane_b32 s9, v88, 48
	v_readlane_b32 s6, v88, 0
	v_readlane_b32 s7, v88, 32
	v_mov_b32_e32 v88, s8
	v_mov_b32_e32 v89, s9
	v_add_f32_e32 v88, s6, v88
	v_add_f32_e32 v89, s7, v89
	s_nop 0
	v_add_f32_e32 v88, v88, v89
	v_fmamk_f32 v88, v88, 0x3a000000, v252
	v_mul_f32_e32 v89, 0x4f800000, v88
	v_cmp_gt_f32_e32 vcc, s55, v88
	s_nop 1
	v_cndmask_b32_e32 v88, v88, v89, vcc
	v_sqrt_f32_e32 v89, v88
	s_nop 0
	v_add_u32_e32 v44, -1, v89
	v_fma_f32 v45, -v44, v89, v88
	v_cmp_ge_f32_e64 s[8:9], 0, v45
	v_add_u32_e32 v45, 1, v89
	s_nop 0
	v_cndmask_b32_e64 v44, v89, v44, s[8:9]
	v_fma_f32 v89, -v45, v89, v88
	v_cmp_lt_f32_e64 s[8:9], 0, v89
	s_nop 1
	v_cndmask_b32_e64 v44, v44, v45, s[8:9]
	v_mul_f32_e32 v45, 0x37800000, v44
	v_cndmask_b32_e32 v44, v44, v45, vcc
	v_cmp_class_f32_e32 vcc, v88, v253
	s_nop 1
	v_cndmask_b32_e32 v44, v44, v88, vcc
	v_div_scale_f32 v45, s[6:7], v44, v44, 1.0
	v_rcp_f32_e32 v104, v45
	global_load_dwordx2 v[122:123], v[42:43], off offset:2048 nt
	global_load_dwordx2 v[110:111], v[42:43], off offset:2560 nt
	global_load_dwordx2 v[94:95], v[42:43], off offset:3072 nt
	global_load_dwordx2 v[88:89], v[42:43], off offset:3584 nt
	v_fma_f32 v42, -v45, v104, 1.0
	v_fmac_f32_e32 v104, v42, v104
	v_div_scale_f32 v42, vcc, 1.0, v44, 1.0
	v_mul_f32_e32 v43, v42, v104
	v_fma_f32 v105, -v45, v43, v42
	v_fmac_f32_e32 v43, v105, v104
	v_fma_f32 v42, -v45, v43, v42
	v_div_fmas_f32 v42, v42, v104, v43
	v_div_fixup_f32 v42, v42, v44, 1.0
	v_mul_f32_e32 v128, v128, v42
	v_mul_f32_e32 v129, v129, v42
	v_mul_f32_e32 v78, v78, v42
	v_mul_f32_e32 v79, v79, v42
	v_lshlrev_b32_e32 v104, 16, v68
	v_and_b32_e32 v105, 0xffff0000, v68
	v_lshlrev_b32_e32 v68, 16, v69
	v_and_b32_e32 v69, 0xffff0000, v69
	v_mul_f32_e32 v78, v2, v78
	v_mul_f32_e32 v79, v3, v79
	v_mul_f32_e32 v128, v4, v128
	v_mul_f32_e32 v129, v5, v129
	v_lshl_add_u64 v[44:45], s[14:15], 1, v[34:35]
	v_mul_f32_e32 v68, v128, v68
	v_mul_f32_e32 v69, v129, v69
	v_mul_f32_e32 v78, v78, v104
	v_mul_f32_e32 v79, v79, v105
	v_lshl_add_u64 v[44:45], v[44:45], 0, v[0:1]
	v_cvt_pk_bf16_f32 v78, v78, v79
	v_cvt_pk_bf16_f32 v79, v68, v69
	global_store_dwordx2 v[44:45], v[78:79], off
	v_mul_f32_e32 v78, v84, v42
	v_mul_f32_e32 v79, v85, v42
	v_mul_f32_e32 v70, v70, v42
	v_mul_f32_e32 v71, v71, v42
	v_lshlrev_b32_e32 v68, 16, v64
	v_and_b32_e32 v69, 0xffff0000, v64
	v_lshlrev_b32_e32 v64, 16, v65
	v_and_b32_e32 v65, 0xffff0000, v65
	v_mul_f32_e32 v70, v6, v70
	v_mul_f32_e32 v71, v7, v71
	v_mul_f32_e32 v78, v8, v78
	v_mul_f32_e32 v79, v9, v79
	v_mul_f32_e32 v68, v70, v68
	v_mul_f32_e32 v69, v71, v69
	v_mul_f32_e32 v64, v78, v64
	v_mul_f32_e32 v65, v79, v65
	v_cvt_pk_bf16_f32 v68, v68, v69
	v_cvt_pk_bf16_f32 v69, v64, v65
	global_store_dwordx2 v[44:45], v[68:69], off offset:512
	v_mul_f32_e32 v68, v134, v42
	v_mul_f32_e32 v69, v135, v42
	v_mul_f32_e32 v70, v130, v42
	v_mul_f32_e32 v71, v131, v42
	v_lshlrev_b32_e32 v64, 16, v58
	v_and_b32_e32 v65, 0xffff0000, v58
	v_lshlrev_b32_e32 v58, 16, v59
	v_and_b32_e32 v59, 0xffff0000, v59
	v_mul_f32_e32 v70, v10, v70
	v_mul_f32_e32 v71, v11, v71
	v_mul_f32_e32 v68, v12, v68
	v_mul_f32_e32 v69, v13, v69
	v_mul_f32_e32 v64, v70, v64
	v_mul_f32_e32 v65, v71, v65
	v_mul_f32_e32 v58, v68, v58
	v_mul_f32_e32 v59, v69, v59
	v_cvt_pk_bf16_f32 v64, v64, v65
	v_cvt_pk_bf16_f32 v65, v58, v59
	global_store_dwordx2 v[44:45], v[64:65], off offset:1024
	v_mul_f32_e32 v64, v114, v42
	v_mul_f32_e32 v65, v115, v42
	v_mul_f32_e32 v68, v124, v42
	v_mul_f32_e32 v69, v125, v42
	v_lshlrev_b32_e32 v58, 16, v62
	v_and_b32_e32 v59, 0xffff0000, v62
	v_lshlrev_b32_e32 v62, 16, v63
	v_and_b32_e32 v63, 0xffff0000, v63
	v_mul_f32_e32 v68, v14, v68
	v_mul_f32_e32 v69, v15, v69
	v_mul_f32_e32 v64, v16, v64
	v_mul_f32_e32 v65, v17, v65
	v_mul_f32_e32 v58, v68, v58
	v_mul_f32_e32 v59, v69, v59
	v_mul_f32_e32 v62, v64, v62
	v_mul_f32_e32 v63, v65, v63
	v_cvt_pk_bf16_f32 v58, v58, v59
	v_cvt_pk_bf16_f32 v59, v62, v63
	v_mul_f32_e32 v62, v112, v42
	v_mul_f32_e32 v63, v113, v42
	v_mul_f32_e32 v64, v166, v42
	v_mul_f32_e32 v65, v167, v42
	global_store_dwordx2 v[44:45], v[58:59], off offset:1536
	v_lshlrev_b32_e32 v58, 16, v56
	v_and_b32_e32 v59, 0xffff0000, v56
	v_lshlrev_b32_e32 v56, 16, v57
	v_and_b32_e32 v57, 0xffff0000, v57
	v_mul_f32_e32 v64, v18, v64
	v_mul_f32_e32 v65, v19, v65
	v_mul_f32_e32 v62, v20, v62
	v_mul_f32_e32 v63, v21, v63
	v_mul_f32_e32 v58, v64, v58
	v_mul_f32_e32 v59, v65, v59
	v_mul_f32_e32 v56, v62, v56
	v_mul_f32_e32 v57, v63, v57
	v_cvt_pk_bf16_f32 v58, v58, v59
	v_cvt_pk_bf16_f32 v59, v56, v57
	global_store_dwordx2 v[44:45], v[58:59], off offset:2048
	v_mul_f32_e32 v58, v102, v42
	v_mul_f32_e32 v59, v103, v42
	v_mul_f32_e32 v62, v116, v42
	v_mul_f32_e32 v63, v117, v42
	v_lshlrev_b32_e32 v56, 16, v52
	v_and_b32_e32 v57, 0xffff0000, v52
	v_lshlrev_b32_e32 v52, 16, v53
	v_and_b32_e32 v53, 0xffff0000, v53
	v_mul_f32_e32 v62, v22, v62
	v_mul_f32_e32 v63, v23, v63
	v_mul_f32_e32 v58, v24, v58
	v_mul_f32_e32 v59, v25, v59
	v_mul_f32_e32 v56, v62, v56
	v_mul_f32_e32 v57, v63, v57
	v_mul_f32_e32 v52, v58, v52
	v_mul_f32_e32 v53, v59, v53
	v_cvt_pk_bf16_f32 v56, v56, v57
	v_cvt_pk_bf16_f32 v57, v52, v53
	global_store_dwordx2 v[44:45], v[56:57], off offset:2560
	v_mul_f32_e32 v56, v92, v42
	v_mul_f32_e32 v57, v93, v42
	v_mul_f32_e32 v58, v132, v42
	v_mul_f32_e32 v59, v133, v42
	v_lshlrev_b32_e32 v52, 16, v48
	v_and_b32_e32 v53, 0xffff0000, v48
	v_lshlrev_b32_e32 v48, 16, v49
	v_and_b32_e32 v49, 0xffff0000, v49
	v_mul_f32_e32 v58, v26, v58
	v_mul_f32_e32 v59, v27, v59
	v_mul_f32_e32 v56, v28, v56
	v_mul_f32_e32 v57, v29, v57
	v_mul_f32_e32 v52, v58, v52
	v_mul_f32_e32 v53, v59, v53
	v_mul_f32_e32 v48, v56, v48
	v_mul_f32_e32 v49, v57, v49
	v_cvt_pk_bf16_f32 v52, v52, v53
	v_cvt_pk_bf16_f32 v53, v48, v49
	global_store_dwordx2 v[44:45], v[52:53], off offset:3072
	v_mul_f32_e32 v52, v86, v42
	v_mul_f32_e32 v53, v87, v42
	v_mul_f32_e32 v43, v137, v42
	v_mul_f32_e32 v42, v136, v42
	s_waitcnt vmcnt(62)
	v_lshlrev_b32_e32 v48, 16, v50
	v_and_b32_e32 v49, 0xffff0000, v50
	v_lshlrev_b32_e32 v50, 16, v51
	v_and_b32_e32 v51, 0xffff0000, v51
	v_mul_f32_e32 v42, v30, v42
	v_mul_f32_e32 v43, v31, v43
	v_mul_f32_e32 v52, v32, v52
	v_mul_f32_e32 v53, v33, v53
	v_mul_f32_e32 v42, v42, v48
	v_mul_f32_e32 v43, v43, v49
	v_mul_f32_e32 v50, v52, v50
	v_mul_f32_e32 v51, v53, v51
	s_add_u32 s14, s12, 0x2800000
	v_cvt_pk_bf16_f32 v42, v42, v43
	v_cvt_pk_bf16_f32 v43, v50, v51
	s_addc_u32 s15, s13, 0
	global_store_dwordx2 v[44:45], v[42:43], off offset:3584
	v_lshl_add_u64 v[42:43], v[36:37], 0, s[14:15]
	v_lshl_add_u64 v[52:53], v[42:43], 0, v[0:1]
	v_lshl_add_u64 v[42:43], v[38:39], 0, s[14:15]
	v_lshl_add_u64 v[48:49], v[42:43], 0, v[0:1]
	v_lshl_add_u64 v[42:43], v[40:41], 0, s[14:15]
	v_lshl_add_u64 v[42:43], v[42:43], 0, v[0:1]
	global_load_dwordx2 v[166:167], v[52:53], off nt
	global_load_dwordx2 v[134:135], v[52:53], off offset:512 nt
	global_load_dwordx2 v[128:129], v[52:53], off offset:1024 nt
	global_load_dwordx2 v[112:113], v[52:53], off offset:1536 nt
	global_load_dwordx2 v[172:173], v[48:49], off nt
	global_load_dwordx2 v[136:137], v[48:49], off offset:512 nt
	global_load_dwordx2 v[130:131], v[48:49], off offset:1024 nt
	global_load_dwordx2 v[114:115], v[48:49], off offset:1536 nt
	global_load_dwordx2 v[62:63], v[42:43], off nt
	global_load_dwordx2 v[56:57], v[42:43], off offset:512 nt
	global_load_dwordx2 v[50:51], v[42:43], off offset:1024 nt
	global_load_dwordx2 v[44:45], v[42:43], off offset:1536 nt
	global_load_dwordx2 v[102:103], v[52:53], off offset:2048 nt
	global_load_dwordx2 v[84:85], v[52:53], off offset:2560 nt
	global_load_dwordx2 v[78:79], v[52:53], off offset:3072 nt
	global_load_dwordx2 v[70:71], v[52:53], off offset:3584 nt
	v_lshlrev_b32_e32 v52, 16, v168
	v_and_b32_e32 v53, 0xffff0000, v168
	s_waitcnt vmcnt(62)
	v_lshlrev_b32_e32 v58, 16, v174
	v_and_b32_e32 v59, 0xffff0000, v174
	v_add_f32_e32 v58, v52, v58
	v_add_f32_e32 v59, v53, v59
	v_lshlrev_b32_e32 v52, 16, v169
	v_and_b32_e32 v53, 0xffff0000, v169
	v_lshlrev_b32_e32 v64, 16, v175
	v_and_b32_e32 v65, 0xffff0000, v175
	v_add_f32_e32 v68, v52, v64
	v_add_f32_e32 v69, v53, v65
	v_lshlrev_b32_e32 v52, 16, v162
	v_and_b32_e32 v53, 0xffff0000, v162
	v_lshlrev_b32_e32 v64, 16, v164
	v_and_b32_e32 v65, 0xffff0000, v164
	v_add_f32_e32 v52, v52, v64
	v_add_f32_e32 v53, v53, v65
	v_lshlrev_b32_e32 v64, 16, v163
	v_and_b32_e32 v65, 0xffff0000, v163
	v_lshlrev_b32_e32 v86, 16, v165
	v_and_b32_e32 v87, 0xffff0000, v165
	v_add_f32_e32 v64, v64, v86
	v_add_f32_e32 v65, v65, v87
	v_mov_b32_e32 v92, v59
	v_mov_b32_e32 v93, v53
	v_mov_b32_e32 v86, v58
	v_mov_b32_e32 v87, v52
	v_mul_f32_e32 v92, v92, v92
	v_mul_f32_e32 v93, v93, v93
	v_mov_b32_e32 v104, v69
	v_mov_b32_e32 v105, v65
	v_fma_f32 v86, v86, v86, v92
	v_fma_f32 v87, v87, v87, v93
	v_mov_b32_e32 v92, v68
	v_mov_b32_e32 v93, v64
	v_mul_f32_e32 v104, v104, v104
	v_mul_f32_e32 v105, v105, v105
	v_lshlrev_b32_e32 v116, 16, v156
	v_fma_f32 v92, v92, v92, v104
	v_fma_f32 v93, v93, v93, v105
	v_lshlrev_b32_e32 v104, 16, v160
	v_add_f32_e32 v86, v86, v92
	v_add_f32_e32 v87, v87, v93
	v_lshlrev_b32_e32 v92, 16, v158
	v_and_b32_e32 v93, 0xffff0000, v158
	v_and_b32_e32 v105, 0xffff0000, v160
	v_add_f32_e32 v124, v92, v104
	v_add_f32_e32 v125, v93, v105
	v_lshlrev_b32_e32 v92, 16, v159
	v_and_b32_e32 v93, 0xffff0000, v159
	v_lshlrev_b32_e32 v104, 16, v161
	v_and_b32_e32 v105, 0xffff0000, v161
	v_add_f32_e32 v158, v92, v104
	v_add_f32_e32 v159, v93, v105
	v_mov_b32_e32 v104, v125
	v_mov_b32_e32 v105, v159
	v_mov_b32_e32 v92, v124
	v_mov_b32_e32 v93, v158
	v_mul_f32_e32 v104, v104, v104
	v_mul_f32_e32 v105, v105, v105
	v_and_b32_e32 v117, 0xffff0000, v156
	v_fma_f32 v92, v92, v92, v104
	v_fma_f32 v93, v93, v93, v105
	v_lshlrev_b32_e32 v104, 16, v154
	v_and_b32_e32 v105, 0xffff0000, v154
	v_add_f32_e32 v132, v104, v116
	v_add_f32_e32 v133, v105, v117
	v_lshlrev_b32_e32 v104, 16, v155
	v_and_b32_e32 v105, 0xffff0000, v155
	v_lshlrev_b32_e32 v116, 16, v157
	v_and_b32_e32 v117, 0xffff0000, v157
	v_lshlrev_b32_e32 v156, 16, v152
	v_and_b32_e32 v157, 0xffff0000, v152
	v_lshlrev_b32_e32 v160, 16, v196
	v_and_b32_e32 v161, 0xffff0000, v196
	v_add_f32_e32 v154, v104, v116
	v_add_f32_e32 v155, v105, v117
	v_add_f32_e32 v162, v156, v160
	v_add_f32_e32 v163, v157, v161
	v_lshlrev_b32_e32 v152, 16, v153
	v_and_b32_e32 v153, 0xffff0000, v153
	v_lshlrev_b32_e32 v156, 16, v197
	v_and_b32_e32 v157, 0xffff0000, v197
	v_mul_f32_e32 v104, v133, v133
	v_mul_f32_e32 v116, v155, v155
	v_add_f32_e32 v168, v152, v156
	v_add_f32_e32 v169, v153, v157
	v_pk_add_f32 v[86:87], v[86:87], v[86:87] op_sel:[0,1] op_sel_hi:[1,0]
	v_pk_add_f32 v[92:93], v[92:93], v[92:93] op_sel:[0,1] op_sel_hi:[1,0]
	v_fma_f32 v105, v133, v133, v104
	v_fma_f32 v104, v132, v132, v104
	v_fma_f32 v117, v155, v155, v116
	v_fma_f32 v116, v154, v154, v116
	v_mul_f32_e32 v152, v162, v162
	v_mul_f32_e32 v153, v163, v163
	v_mul_f32_e32 v156, v168, v168
	v_mul_f32_e32 v157, v169, v169
	v_mov_b32_e32 v87, v152
	v_mov_b32_e32 v93, v153
	v_mov_b32_e32 v105, v156
	v_mov_b32_e32 v117, v157
	v_add_f32_e32 v86, v86, v92
	v_add_f32_e32 v87, v87, v93
	v_add_f32_e32 v92, v104, v116
	v_add_f32_e32 v93, v105, v117
	v_lshlrev_b32_e32 v104, 16, v192
	v_add_f32_e32 v86, v86, v92
	v_add_f32_e32 v87, v87, v93
	v_lshlrev_b32_e32 v92, 16, v150
	v_and_b32_e32 v93, 0xffff0000, v150
	v_and_b32_e32 v105, 0xffff0000, v192
	v_add_f32_e32 v174, v92, v104
	v_add_f32_e32 v175, v93, v105
	v_lshlrev_b32_e32 v92, 16, v151
	v_and_b32_e32 v93, 0xffff0000, v151
	v_lshlrev_b32_e32 v104, 16, v193
	v_and_b32_e32 v105, 0xffff0000, v193
	v_add_f32_e32 v150, v92, v104
	v_add_f32_e32 v151, v93, v105
	v_mov_b32_e32 v104, v175
	v_mov_b32_e32 v105, v151
	v_mov_b32_e32 v92, v174
	v_mov_b32_e32 v93, v150
	v_mul_f32_e32 v104, v104, v104
	v_mul_f32_e32 v105, v105, v105
	s_waitcnt vmcnt(61)
	v_lshlrev_b32_e32 v116, 16, v188
	v_fma_f32 v92, v92, v92, v104
	v_fma_f32 v93, v93, v93, v105
	v_lshlrev_b32_e32 v104, 16, v148
	v_and_b32_e32 v105, 0xffff0000, v148
	v_and_b32_e32 v117, 0xffff0000, v188
	v_add_f32_e32 v178, v104, v116
	v_add_f32_e32 v179, v105, v117
	v_lshlrev_b32_e32 v104, 16, v149
	v_and_b32_e32 v105, 0xffff0000, v149
	v_lshlrev_b32_e32 v116, 16, v189
	v_and_b32_e32 v117, 0xffff0000, v189
	v_lshlrev_b32_e32 v152, 16, v140
	v_and_b32_e32 v153, 0xffff0000, v140
	s_waitcnt vmcnt(60)
; template <int CTRL> __device__ __forceinline__ float dpp_mov(float v) { return __builtin_bit_cast(float, __builtin_amdgcn_update_dpp(0, __builtin_bit_cast(int, v), CTRL, 0xF, 0xF, true)); }
; __device__ __forceinline__ float wave_sum(float v) {
;     v += dpp_mov<0xB1>(v);
;     v += dpp_mov<0x4E>(v);
;     v += dpp_mov<0x141>(v);
;     v += dpp_mov<0x140>(v);
;     const int iv = __builtin_bit_cast(int, v);
;     const float a = __builtin_bit_cast(float, __builtin_amdgcn_readlane(iv, 0)), b = __builtin_bit_cast(float, __builtin_amdgcn_readlane(iv, 16));
;     const float c = __builtin_bit_cast(float, __builtin_amdgcn_readlane(iv, 32)), d = __builtin_bit_cast(float, __builtin_amdgcn_readlane(iv, 48));
;     return (a + b) + (c + d);
; }
	v_lshlrev_b32_e32 v156, 16, v184
	v_and_b32_e32 v157, 0xffff0000, v184
	v_add_f32_e32 v148, v104, v116
	v_add_f32_e32 v149, v105, v117
	v_add_f32_e32 v180, v152, v156
	v_add_f32_e32 v181, v153, v157
	v_lshlrev_b32_e32 v140, 16, v141
	v_and_b32_e32 v141, 0xffff0000, v141
	v_lshlrev_b32_e32 v152, 16, v185
	v_and_b32_e32 v153, 0xffff0000, v185
	v_mul_f32_e32 v104, v179, v179
	v_mul_f32_e32 v116, v149, v149
	v_add_f32_e32 v140, v140, v152
	v_add_f32_e32 v141, v141, v153
	v_pk_add_f32 v[86:87], v[86:87], v[86:87] op_sel:[0,1] op_sel_hi:[1,0]
	v_pk_add_f32 v[92:93], v[92:93], v[92:93] op_sel:[0,1] op_sel_hi:[1,0]
	v_fma_f32 v105, v179, v179, v104
	v_fma_f32 v104, v178, v178, v104
	v_fma_f32 v117, v149, v149, v116
	v_fma_f32 v116, v148, v148, v116
	v_mul_f32_e32 v152, v180, v180
	v_mul_f32_e32 v153, v181, v181
	v_mul_f32_e32 v156, v140, v140
	v_mul_f32_e32 v157, v141, v141
	v_mov_b32_e32 v87, v152
	v_mov_b32_e32 v93, v153
	v_mov_b32_e32 v105, v156
	v_mov_b32_e32 v117, v157
	v_add_f32_e32 v86, v86, v92
	v_add_f32_e32 v87, v87, v93
	v_add_f32_e32 v92, v104, v116
	v_add_f32_e32 v93, v105, v117
	global_load_dwordx2 v[164:165], v[48:49], off offset:2048 nt
	global_load_dwordx2 v[160:161], v[48:49], off offset:2560 nt
	global_load_dwordx2 v[156:157], v[48:49], off offset:3072 nt
	global_load_dwordx2 v[152:153], v[48:49], off offset:3584 nt
	v_add_f32_e32 v86, v86, v92
	v_add_f32_e32 v87, v87, v93
	s_add_u32 s12, s12, 0x3000000
	v_add_f32_e32 v86, v86, v87
	s_addc_u32 s13, s13, 0
	s_nop 0
	v_add_f32_dpp v86, v86, v86 quad_perm:[1,0,3,2] row_mask:0xf bank_mask:0xf bound_ctrl:1
	s_nop 1
	v_add_f32_dpp v86, v86, v86 quad_perm:[2,3,0,1] row_mask:0xf bank_mask:0xf bound_ctrl:1
	s_nop 1
	v_add_f32_dpp v86, v86, v86 row_half_mirror row_mask:0xf bank_mask:0xf bound_ctrl:1
	s_nop 1
	v_add_f32_dpp v86, v86, v86 row_mirror row_mask:0xf bank_mask:0xf bound_ctrl:1
	s_nop 0
	v_readlane_b32 s8, v86, 16
	v_readlane_b32 s9, v86, 48
	v_readlane_b32 s6, v86, 0
	v_readlane_b32 s7, v86, 32
	v_mov_b32_e32 v86, s8
	v_mov_b32_e32 v87, s9
	v_add_f32_e32 v86, s6, v86
	v_add_f32_e32 v87, s7, v87
	s_nop 0
	v_add_f32_e32 v86, v86, v87
	v_fmamk_f32 v86, v86, 0x3a000000, v252
	v_mul_f32_e32 v87, 0x4f800000, v86
	v_cmp_gt_f32_e32 vcc, s55, v86
	s_nop 1
	v_cndmask_b32_e32 v86, v86, v87, vcc
	v_sqrt_f32_e32 v87, v86
	s_nop 0
	v_add_u32_e32 v48, -1, v87
	v_fma_f32 v49, -v48, v87, v86
	v_cmp_ge_f32_e64 s[8:9], 0, v49
	v_add_u32_e32 v49, 1, v87
	s_nop 0
	v_cndmask_b32_e64 v48, v87, v48, s[8:9]
	v_fma_f32 v87, -v49, v87, v86
	v_cmp_lt_f32_e64 s[8:9], 0, v87
	s_nop 1
	v_cndmask_b32_e64 v48, v48, v49, s[8:9]
	v_mul_f32_e32 v49, 0x37800000, v48
	v_cndmask_b32_e32 v48, v48, v49, vcc
	v_cmp_class_f32_e32 vcc, v86, v253
	s_nop 1
	v_cndmask_b32_e32 v48, v48, v86, vcc
	v_div_scale_f32 v49, s[6:7], v48, v48, 1.0
	v_rcp_f32_e32 v184, v49
	global_load_dwordx2 v[116:117], v[42:43], off offset:2048 nt
	global_load_dwordx2 v[104:105], v[42:43], off offset:2560 nt
	global_load_dwordx2 v[92:93], v[42:43], off offset:3072 nt
	global_load_dwordx2 v[86:87], v[42:43], off offset:3584 nt
	v_fma_f32 v42, -v49, v184, 1.0
	v_fmac_f32_e32 v184, v42, v184
	v_div_scale_f32 v42, vcc, 1.0, v48, 1.0
	v_mul_f32_e32 v43, v42, v184
	v_fma_f32 v185, -v49, v43, v42
	v_fmac_f32_e32 v43, v185, v184
	v_fma_f32 v42, -v49, v43, v42
	v_div_fmas_f32 v42, v42, v184, v43
	v_div_fixup_f32 v42, v42, v48, 1.0
	v_mul_f32_e32 v68, v68, v42
	v_mul_f32_e32 v69, v69, v42
	v_mul_f32_e32 v58, v58, v42
	v_mul_f32_e32 v59, v59, v42
	v_lshlrev_b32_e32 v184, 16, v100
	v_and_b32_e32 v185, 0xffff0000, v100
	v_lshlrev_b32_e32 v100, 16, v101
	v_and_b32_e32 v101, 0xffff0000, v101
	v_mul_f32_e32 v58, v2, v58
	v_mul_f32_e32 v59, v3, v59
	v_mul_f32_e32 v68, v4, v68
	v_mul_f32_e32 v69, v5, v69
	v_lshl_add_u64 v[48:49], v[34:35], 0, s[16:17]
	v_mul_f32_e32 v68, v68, v100
	v_mul_f32_e32 v69, v69, v101
	v_mul_f32_e32 v58, v58, v184
	v_mul_f32_e32 v59, v59, v185
	v_lshl_add_u64 v[48:49], v[48:49], 0, v[0:1]
	v_cvt_pk_bf16_f32 v58, v58, v59
	v_cvt_pk_bf16_f32 v59, v68, v69
	v_mul_f32_e32 v64, v64, v42
	v_mul_f32_e32 v65, v65, v42
	v_mul_f32_e32 v52, v52, v42
	v_mul_f32_e32 v53, v53, v42
	global_store_dwordx2 v[48:49], v[58:59], off
	v_lshlrev_b32_e32 v58, 16, v90
	v_and_b32_e32 v59, 0xffff0000, v90
	v_lshlrev_b32_e32 v68, 16, v91
	v_and_b32_e32 v69, 0xffff0000, v91
	v_mul_f32_e32 v52, v6, v52
	v_mul_f32_e32 v53, v7, v53
	v_mul_f32_e32 v64, v8, v64
	v_mul_f32_e32 v65, v9, v65
	v_mul_f32_e32 v52, v52, v58
	v_mul_f32_e32 v53, v53, v59
	v_mul_f32_e32 v64, v64, v68
	v_mul_f32_e32 v65, v65, v69
	v_cvt_pk_bf16_f32 v52, v52, v53
	v_cvt_pk_bf16_f32 v53, v64, v65
	v_mul_f32_e32 v64, v158, v42
	v_mul_f32_e32 v65, v159, v42
	v_mul_f32_e32 v68, v124, v42
	v_mul_f32_e32 v69, v125, v42
	global_store_dwordx2 v[48:49], v[52:53], off offset:512
	v_lshlrev_b32_e32 v52, 16, v80
	v_and_b32_e32 v53, 0xffff0000, v80
	v_lshlrev_b32_e32 v58, 16, v81
	v_and_b32_e32 v59, 0xffff0000, v81
	v_mul_f32_e32 v68, v10, v68
	v_mul_f32_e32 v69, v11, v69
	v_mul_f32_e32 v64, v12, v64
	v_mul_f32_e32 v65, v13, v65
	v_mul_f32_e32 v52, v68, v52
	v_mul_f32_e32 v53, v69, v53
	v_mul_f32_e32 v58, v64, v58
	v_mul_f32_e32 v59, v65, v59
	v_cvt_pk_bf16_f32 v52, v52, v53
	v_cvt_pk_bf16_f32 v53, v58, v59
	v_mul_f32_e32 v64, v154, v42
	v_mul_f32_e32 v65, v155, v42
	v_mul_f32_e32 v68, v132, v42
	v_mul_f32_e32 v69, v133, v42
	global_store_dwordx2 v[48:49], v[52:53], off offset:1024
	v_lshlrev_b32_e32 v52, 16, v76
	v_and_b32_e32 v53, 0xffff0000, v76
	v_lshlrev_b32_e32 v58, 16, v77
	v_and_b32_e32 v59, 0xffff0000, v77
	v_mul_f32_e32 v68, v14, v68
	v_mul_f32_e32 v69, v15, v69
	v_mul_f32_e32 v64, v16, v64
	v_mul_f32_e32 v65, v17, v65
	v_mul_f32_e32 v52, v68, v52
	v_mul_f32_e32 v53, v69, v53
	v_mul_f32_e32 v58, v64, v58
	v_mul_f32_e32 v59, v65, v59
	v_mul_f32_e32 v64, v168, v42
	v_mul_f32_e32 v65, v169, v42
	v_cvt_pk_bf16_f32 v52, v52, v53
	v_cvt_pk_bf16_f32 v53, v58, v59
	s_waitcnt vmcnt(62)
	v_lshlrev_b32_e32 v58, 16, v127
	v_and_b32_e32 v59, 0xffff0000, v127
	v_mul_f32_e32 v68, v162, v42
	v_mul_f32_e32 v69, v163, v42
	v_mul_f32_e32 v64, v20, v64
	v_mul_f32_e32 v65, v21, v65
	global_store_dwordx2 v[48:49], v[52:53], off offset:1536
	v_lshlrev_b32_e32 v52, 16, v126
	v_and_b32_e32 v53, 0xffff0000, v126
	v_mul_f32_e32 v68, v18, v68
	v_mul_f32_e32 v69, v19, v69
	v_mul_f32_e32 v58, v64, v58
	v_mul_f32_e32 v59, v65, v59
	v_mul_f32_e32 v64, v150, v42
	v_mul_f32_e32 v65, v151, v42
	s_waitcnt vmcnt(59)
	v_lshlrev_b32_e32 v150, 16, v170
	v_and_b32_e32 v151, 0xffff0000, v170
	s_waitcnt vmcnt(55)
	v_lshlrev_b32_e32 v154, 16, v176
	v_and_b32_e32 v155, 0xffff0000, v176
	v_mul_f32_e32 v52, v68, v52
	v_mul_f32_e32 v53, v69, v53
	v_mul_f32_e32 v68, v174, v42
	v_mul_f32_e32 v69, v175, v42
	v_add_f32_e32 v174, v150, v154
	v_add_f32_e32 v175, v151, v155
	v_lshlrev_b32_e32 v150, 16, v171
	v_and_b32_e32 v151, 0xffff0000, v171
	v_lshlrev_b32_e32 v154, 16, v177
	v_and_b32_e32 v155, 0xffff0000, v177
	v_add_f32_e32 v170, v150, v154
	v_add_f32_e32 v171, v151, v155
	v_lshlrev_b32_e32 v150, 16, v144
	v_and_b32_e32 v151, 0xffff0000, v144
	s_waitcnt vmcnt(54)
	v_lshlrev_b32_e32 v154, 16, v146
	v_and_b32_e32 v155, 0xffff0000, v146
	v_add_f32_e32 v168, v150, v154
	v_add_f32_e32 v169, v151, v155
	v_lshlrev_b32_e32 v144, 16, v145
	v_and_b32_e32 v145, 0xffff0000, v145
	v_lshlrev_b32_e32 v146, 16, v147
	v_and_b32_e32 v147, 0xffff0000, v147
	v_add_f32_e32 v144, v144, v146
	v_add_f32_e32 v145, v145, v147
	v_mov_b32_e32 v150, v175
	v_mov_b32_e32 v151, v169
	v_mov_b32_e32 v146, v174
	v_mov_b32_e32 v147, v168
	v_mul_f32_e32 v150, v150, v150
	v_mul_f32_e32 v151, v151, v151
	v_mov_b32_e32 v154, v171
	v_mov_b32_e32 v155, v145
	v_fma_f32 v146, v146, v146, v150
	v_fma_f32 v147, v147, v147, v151
	v_mov_b32_e32 v150, v170
	v_mov_b32_e32 v151, v144
	v_mul_f32_e32 v154, v154, v154
	v_mul_f32_e32 v155, v155, v155
	v_cvt_pk_bf16_f32 v52, v52, v53
	v_fma_f32 v150, v150, v150, v154
	v_fma_f32 v151, v151, v151, v155
	s_waitcnt vmcnt(53)
	v_lshlrev_b32_e32 v154, 16, v142
	v_add_f32_e32 v146, v146, v150
	v_add_f32_e32 v147, v147, v151
	v_and_b32_e32 v155, 0xffff0000, v142
	v_add_f32_e32 v150, v146, v147
	v_add_f32_e32 v151, v147, v146
	v_lshlrev_b32_e32 v146, 16, v138
	v_and_b32_e32 v147, 0xffff0000, v138
	v_lshlrev_b32_e32 v138, 16, v139
	v_and_b32_e32 v139, 0xffff0000, v139
	v_lshlrev_b32_e32 v142, 16, v143
	v_and_b32_e32 v143, 0xffff0000, v143
	v_add_f32_e32 v146, v146, v154
	v_add_f32_e32 v147, v147, v155
	v_add_f32_e32 v142, v138, v142
	v_add_f32_e32 v143, v139, v143
	v_mov_b32_e32 v154, v147
	v_mov_b32_e32 v155, v143
	v_mov_b32_e32 v138, v146
	v_mov_b32_e32 v139, v142
	v_mul_f32_e32 v154, v154, v154
	v_mul_f32_e32 v155, v155, v155
	v_cvt_pk_bf16_f32 v53, v58, v59
	v_fma_f32 v138, v138, v138, v154
	v_fma_f32 v139, v139, v139, v155
	s_waitcnt vmcnt(52)
	v_lshlrev_b32_e32 v158, 16, v120
	v_add_f32_e32 v154, v138, v139
	v_add_f32_e32 v155, v139, v138
	v_lshlrev_b32_e32 v138, 16, v118
	v_and_b32_e32 v139, 0xffff0000, v118
	v_and_b32_e32 v159, 0xffff0000, v120
	v_lshlrev_b32_e32 v118, 16, v119
	v_and_b32_e32 v119, 0xffff0000, v119
	v_lshlrev_b32_e32 v120, 16, v121
	v_and_b32_e32 v121, 0xffff0000, v121
	s_waitcnt vmcnt(47)
	v_lshlrev_b32_e32 v162, 16, v106
	v_and_b32_e32 v163, 0xffff0000, v106
	s_waitcnt vmcnt(43)
	v_lshlrev_b32_e32 v176, 16, v198
	v_and_b32_e32 v177, 0xffff0000, v198
	global_store_dwordx2 v[48:49], v[52:53], off offset:2048
	v_lshlrev_b32_e32 v52, 16, v108
	v_and_b32_e32 v53, 0xffff0000, v108
	v_mul_f32_e32 v68, v22, v68
	v_mul_f32_e32 v69, v23, v69
	v_add_f32_e32 v138, v138, v158
	v_add_f32_e32 v139, v139, v159
	v_add_f32_e32 v118, v118, v120
	v_add_f32_e32 v119, v119, v121
	v_add_f32_e32 v176, v162, v176
	v_add_f32_e32 v177, v163, v177
	v_lshlrev_b32_e32 v106, 16, v107
	v_and_b32_e32 v107, 0xffff0000, v107
	v_lshlrev_b32_e32 v162, 16, v199
	v_and_b32_e32 v163, 0xffff0000, v199
	v_mul_f32_e32 v52, v68, v52
	v_mul_f32_e32 v53, v69, v53
	v_mul_f32_e32 v68, v178, v42
	v_mul_f32_e32 v69, v179, v42
	v_mul_f32_e32 v120, v139, v139
	v_mul_f32_e32 v158, v119, v119
	v_add_f32_e32 v178, v106, v162
	v_add_f32_e32 v179, v107, v163
	v_fma_f32 v121, v139, v139, v120
	v_fma_f32 v120, v138, v138, v120
	v_fma_f32 v159, v119, v119, v158
	v_fma_f32 v158, v118, v118, v158
	v_mul_f32_e32 v106, v176, v176
	v_mul_f32_e32 v107, v177, v177
	v_mul_f32_e32 v162, v178, v178
	v_mul_f32_e32 v163, v179, v179
	v_mov_b32_e32 v151, v106
	v_mov_b32_e32 v155, v107
	v_mov_b32_e32 v121, v162
	v_mov_b32_e32 v159, v163
	v_lshlrev_b32_e32 v58, 16, v109
	v_and_b32_e32 v59, 0xffff0000, v109
	v_mul_f32_e32 v64, v24, v64
	v_mul_f32_e32 v65, v25, v65
	v_add_f32_e32 v106, v150, v154
	v_add_f32_e32 v107, v151, v155
	v_add_f32_e32 v120, v120, v158
	v_add_f32_e32 v121, v121, v159
	v_mul_f32_e32 v58, v64, v58
	v_mul_f32_e32 v59, v65, v59
	v_mul_f32_e32 v64, v148, v42
	v_mul_f32_e32 v65, v149, v42
	v_add_f32_e32 v106, v106, v120
	v_add_f32_e32 v107, v107, v121
	v_lshlrev_b32_e32 v120, 16, v96
	v_and_b32_e32 v121, 0xffff0000, v96
	s_waitcnt vmcnt(43)
	v_lshlrev_b32_e32 v150, 16, v194
	v_and_b32_e32 v151, 0xffff0000, v194
	v_cvt_pk_bf16_f32 v52, v52, v53
	v_cvt_pk_bf16_f32 v53, v58, v59
	v_lshlrev_b32_e32 v58, 16, v99
	v_and_b32_e32 v59, 0xffff0000, v99
	v_mul_f32_e32 v64, v28, v64
	v_mul_f32_e32 v65, v29, v65
	v_add_f32_e32 v120, v120, v150
	v_add_f32_e32 v121, v121, v151
	v_lshlrev_b32_e32 v96, 16, v97
	v_and_b32_e32 v97, 0xffff0000, v97
	v_lshlrev_b32_e32 v150, 16, v195
	v_and_b32_e32 v151, 0xffff0000, v195
	v_mul_f32_e32 v58, v64, v58
	v_mul_f32_e32 v59, v65, v59
	v_mul_f32_e32 v64, v140, v42
	v_mul_f32_e32 v65, v141, v42
	v_mul_f32_e32 v43, v181, v42
	v_mul_f32_e32 v42, v180, v42
	v_add_f32_e32 v180, v96, v150
	v_add_f32_e32 v181, v97, v151
	v_mov_b32_e32 v150, v121
	v_mov_b32_e32 v151, v181
	v_mov_b32_e32 v96, v120
	v_mov_b32_e32 v97, v180
	v_mul_f32_e32 v150, v150, v150
	v_mul_f32_e32 v151, v151, v151
	s_waitcnt vmcnt(42)
; template <int CTRL> __device__ __forceinline__ float dpp_mov(float v) { return __builtin_bit_cast(float, __builtin_amdgcn_update_dpp(0, __builtin_bit_cast(int, v), CTRL, 0xF, 0xF, true)); }
; __device__ __forceinline__ float wave_sum(float v) {
;     v += dpp_mov<0xB1>(v);
;     v += dpp_mov<0x4E>(v);
;     v += dpp_mov<0x141>(v);
;     v += dpp_mov<0x140>(v);
;     const int iv = __builtin_bit_cast(int, v);
;     const float a = __builtin_bit_cast(float, __builtin_amdgcn_readlane(iv, 0)), b = __builtin_bit_cast(float, __builtin_amdgcn_readlane(iv, 16));
;     const float c = __builtin_bit_cast(float, __builtin_amdgcn_readlane(iv, 32)), d = __builtin_bit_cast(float, __builtin_amdgcn_readlane(iv, 48));
;     return (a + b) + (c + d);
; }
	v_lshlrev_b32_e32 v154, 16, v190
	v_fma_f32 v96, v96, v96, v150
	v_fma_f32 v97, v97, v97, v151
	v_lshlrev_b32_e32 v150, 16, v82
	v_and_b32_e32 v151, 0xffff0000, v82
	v_and_b32_e32 v155, 0xffff0000, v190
	v_add_f32_e32 v184, v150, v154
	v_add_f32_e32 v185, v151, v155
	v_lshlrev_b32_e32 v82, 16, v83
	v_and_b32_e32 v83, 0xffff0000, v83
	v_lshlrev_b32_e32 v150, 16, v191
	v_and_b32_e32 v151, 0xffff0000, v191
	v_lshlrev_b32_e32 v154, 16, v72
	v_and_b32_e32 v155, 0xffff0000, v72
	s_waitcnt vmcnt(41)
	v_lshlrev_b32_e32 v158, 16, v186
	v_and_b32_e32 v159, 0xffff0000, v186
	v_add_f32_e32 v188, v82, v150
	v_add_f32_e32 v189, v83, v151
	v_add_f32_e32 v190, v154, v158
	v_add_f32_e32 v191, v155, v159
	v_lshlrev_b32_e32 v72, 16, v73
	v_and_b32_e32 v73, 0xffff0000, v73
	v_lshlrev_b32_e32 v154, 16, v187
	v_and_b32_e32 v155, 0xffff0000, v187
	v_mul_f32_e32 v82, v185, v185
	v_mul_f32_e32 v150, v189, v189
	v_add_f32_e32 v186, v72, v154
	v_add_f32_e32 v187, v73, v155
	v_pk_add_f32 v[106:107], v[106:107], v[106:107] op_sel:[0,1] op_sel_hi:[1,0]
	v_pk_add_f32 v[96:97], v[96:97], v[96:97] op_sel:[0,1] op_sel_hi:[1,0]
	v_fma_f32 v83, v185, v185, v82
	v_fma_f32 v82, v184, v184, v82
	v_fma_f32 v151, v189, v189, v150
	v_fma_f32 v150, v188, v188, v150
	v_mul_f32_e32 v72, v190, v190
	v_mul_f32_e32 v73, v191, v191
	v_mul_f32_e32 v154, v186, v186
	v_mul_f32_e32 v155, v187, v187
	v_mov_b32_e32 v107, v72
	v_mov_b32_e32 v97, v73
	v_mov_b32_e32 v83, v154
	v_mov_b32_e32 v151, v155
	v_add_f32_e32 v72, v106, v96
	v_add_f32_e32 v73, v107, v97
	v_add_f32_e32 v82, v82, v150
	v_add_f32_e32 v83, v83, v151
	global_store_dwordx2 v[48:49], v[52:53], off offset:2560
	v_add_f32_e32 v72, v72, v82
	v_add_f32_e32 v73, v73, v83
	v_lshlrev_b32_e32 v52, 16, v98
	v_add_f32_e32 v72, v72, v73
	v_and_b32_e32 v53, 0xffff0000, v98
	v_mul_f32_e32 v68, v26, v68
	v_mul_f32_e32 v69, v27, v69
	v_add_f32_dpp v72, v72, v72 quad_perm:[1,0,3,2] row_mask:0xf bank_mask:0xf bound_ctrl:1
	v_mul_f32_e32 v52, v68, v52
	v_mul_f32_e32 v53, v69, v53
	v_mul_f32_e32 v42, v30, v42
	v_mul_f32_e32 v43, v31, v43
	v_add_f32_dpp v72, v72, v72 quad_perm:[2,3,0,1] row_mask:0xf bank_mask:0xf bound_ctrl:1
	v_cvt_pk_bf16_f32 v52, v52, v53
	v_cvt_pk_bf16_f32 v53, v58, v59
	v_add_f32_dpp v72, v72, v72 row_half_mirror row_mask:0xf bank_mask:0xf bound_ctrl:1
	global_store_dwordx2 v[48:49], v[52:53], off offset:3072
	v_lshlrev_b32_e32 v52, 16, v74
	v_add_f32_dpp v72, v72, v72 row_mirror row_mask:0xf bank_mask:0xf bound_ctrl:1
	v_and_b32_e32 v53, 0xffff0000, v74
	v_readlane_b32 s8, v72, 16
	v_readlane_b32 s9, v72, 48
	v_readlane_b32 s6, v72, 0
	v_readlane_b32 s7, v72, 32
	v_mov_b32_e32 v72, s8
	v_mov_b32_e32 v73, s9
	v_add_f32_e32 v72, s6, v72
	v_add_f32_e32 v73, s7, v73
	v_lshlrev_b32_e32 v58, 16, v75
	v_add_f32_e32 v72, v72, v73
	v_fmamk_f32 v72, v72, 0x3a000000, v252
	v_and_b32_e32 v59, 0xffff0000, v75
	v_mul_f32_e32 v64, v32, v64
	v_mul_f32_e32 v65, v33, v65
	v_mul_f32_e32 v73, 0x4f800000, v72
	v_cmp_gt_f32_e32 vcc, s55, v72
	v_mul_f32_e32 v58, v64, v58
	v_mul_f32_e32 v59, v65, v59
	v_mul_f32_e32 v42, v42, v52
	v_mul_f32_e32 v43, v43, v53
	v_cndmask_b32_e32 v72, v72, v73, vcc
	v_cvt_pk_bf16_f32 v42, v42, v43
	v_cvt_pk_bf16_f32 v43, v58, v59
	v_sqrt_f32_e32 v73, v72
	global_store_dwordx2 v[48:49], v[42:43], off offset:3584
	v_lshl_add_u64 v[42:43], v[36:37], 0, s[12:13]
	v_lshl_add_u64 v[68:69], v[42:43], 0, v[0:1]
	v_lshl_add_u64 v[42:43], v[38:39], 0, s[12:13]
	v_lshl_add_u64 v[80:81], v[42:43], 0, v[0:1]
	v_lshl_add_u64 v[42:43], v[40:41], 0, s[12:13]
	v_lshl_add_u64 v[64:65], v[42:43], 0, v[0:1]
	global_load_dwordx2 v[140:141], v[68:69], off nt
	global_load_dwordx2 v[126:127], v[68:69], off offset:512 nt
	global_load_dwordx2 v[108:109], v[68:69], off offset:1024 nt
	global_load_dwordx2 v[98:99], v[68:69], off offset:1536 nt
	global_load_dwordx2 v[148:149], v[80:81], off nt
	global_load_dwordx2 v[132:133], v[80:81], off offset:512 nt
	global_load_dwordx2 v[124:125], v[80:81], off offset:1024 nt
	global_load_dwordx2 v[100:101], v[80:81], off offset:1536 nt
	global_load_dwordx2 v[58:59], v[64:65], off nt
	global_load_dwordx2 v[52:53], v[64:65], off offset:512 nt
	global_load_dwordx2 v[48:49], v[64:65], off offset:1024 nt
	global_load_dwordx2 v[42:43], v[64:65], off offset:1536 nt
	global_load_dwordx2 v[90:91], v[68:69], off offset:2048 nt
	global_load_dwordx2 v[76:77], v[68:69], off offset:2560 nt
	global_load_dwordx2 v[74:75], v[68:69], off offset:3072 nt
	s_nop 0
	global_load_dwordx2 v[68:69], v[68:69], off offset:3584 nt
	s_nop 0
	global_load_dwordx2 v[162:163], v[80:81], off offset:2048 nt
	global_load_dwordx2 v[158:159], v[80:81], off offset:2560 nt
	global_load_dwordx2 v[154:155], v[80:81], off offset:3072 nt
	global_load_dwordx2 v[150:151], v[80:81], off offset:3584 nt
	v_add_u32_e32 v80, -1, v73
	v_fma_f32 v81, -v80, v73, v72
	v_cmp_ge_f32_e64 s[8:9], 0, v81
	v_add_u32_e32 v81, 1, v73
	s_nop 0
	v_cndmask_b32_e64 v80, v73, v80, s[8:9]
	v_fma_f32 v73, -v81, v73, v72
	v_cmp_lt_f32_e64 s[8:9], 0, v73
	s_nop 1
	v_cndmask_b32_e64 v73, v80, v81, s[8:9]
	v_mul_f32_e32 v80, 0x37800000, v73
	v_cndmask_b32_e32 v73, v73, v80, vcc
	v_cmp_class_f32_e32 vcc, v72, v253
	s_nop 1
	v_cndmask_b32_e32 v80, v73, v72, vcc
	v_div_scale_f32 v81, s[6:7], v80, v80, 1.0
	v_rcp_f32_e32 v192, v81
	global_load_dwordx2 v[106:107], v[64:65], off offset:2048 nt
	global_load_dwordx2 v[96:97], v[64:65], off offset:2560 nt
	global_load_dwordx2 v[82:83], v[64:65], off offset:3072 nt
	global_load_dwordx2 v[72:73], v[64:65], off offset:3584 nt
	v_fma_f32 v64, -v81, v192, 1.0
	v_fmac_f32_e32 v192, v64, v192
	v_div_scale_f32 v64, vcc, 1.0, v80, 1.0
	v_mul_f32_e32 v65, v64, v192
	v_fma_f32 v193, -v81, v65, v64
	v_fmac_f32_e32 v65, v193, v192
	v_fma_f32 v64, -v81, v65, v64
	v_div_fmas_f32 v64, v64, v192, v65
	v_div_fixup_f32 v64, v64, v80, 1.0
	v_mul_f32_e32 v170, v170, v64
	v_mul_f32_e32 v171, v171, v64
	v_mul_f32_e32 v174, v174, v64
	v_mul_f32_e32 v175, v175, v64
	v_lshlrev_b32_e32 v192, 16, v66
	v_and_b32_e32 v193, 0xffff0000, v66
	v_lshlrev_b32_e32 v66, 16, v67
	v_and_b32_e32 v67, 0xffff0000, v67
	v_mul_f32_e32 v174, v2, v174
	v_mul_f32_e32 v175, v3, v175
	v_mul_f32_e32 v170, v4, v170
	v_mul_f32_e32 v171, v5, v171
	v_mul_f32_e32 v144, v144, v64
	v_mul_f32_e32 v145, v145, v64
	v_mul_f32_e32 v66, v170, v66
	v_mul_f32_e32 v67, v171, v67
	v_mul_f32_e32 v170, v174, v192
	v_mul_f32_e32 v171, v175, v193
	v_mul_f32_e32 v168, v168, v64
	v_mul_f32_e32 v169, v169, v64
	v_cvt_pk_bf16_f32 v170, v170, v171
	v_cvt_pk_bf16_f32 v171, v66, v67
	v_lshlrev_b32_e32 v66, 16, v60
	v_and_b32_e32 v67, 0xffff0000, v60
	v_lshlrev_b32_e32 v60, 16, v61
	v_and_b32_e32 v61, 0xffff0000, v61
	v_mul_f32_e32 v168, v6, v168
	v_mul_f32_e32 v169, v7, v169
	v_mul_f32_e32 v144, v8, v144
	v_mul_f32_e32 v145, v9, v145
	v_lshl_add_u64 v[80:81], v[34:35], 0, s[18:19]
	v_mul_f32_e32 v60, v144, v60
	v_mul_f32_e32 v61, v145, v61
	v_mul_f32_e32 v66, v168, v66
	v_mul_f32_e32 v67, v169, v67
	v_lshl_add_u64 v[80:81], v[80:81], 0, v[0:1]
	v_cvt_pk_bf16_f32 v66, v66, v67
	v_cvt_pk_bf16_f32 v67, v60, v61
	global_store_dwordx2 v[80:81], v[66:67], off offset:512
	v_mul_f32_e32 v66, v142, v64
	v_mul_f32_e32 v67, v143, v64
	v_mul_f32_e32 v142, v146, v64
	v_mul_f32_e32 v143, v147, v64
	v_lshlrev_b32_e32 v60, 16, v54
	v_and_b32_e32 v61, 0xffff0000, v54
	v_lshlrev_b32_e32 v54, 16, v55
	v_and_b32_e32 v55, 0xffff0000, v55
	v_mul_f32_e32 v142, v10, v142
	v_mul_f32_e32 v143, v11, v143
	v_mul_f32_e32 v66, v12, v66
	v_mul_f32_e32 v67, v13, v67
	v_mul_f32_e32 v60, v142, v60
	v_mul_f32_e32 v61, v143, v61
	v_mul_f32_e32 v54, v66, v54
	v_mul_f32_e32 v55, v67, v55
	v_mul_f32_e32 v66, v138, v64
	v_mul_f32_e32 v67, v139, v64
	v_cvt_pk_bf16_f32 v60, v60, v61
	v_cvt_pk_bf16_f32 v61, v54, v55
	v_lshlrev_b32_e32 v54, 16, v46
	v_and_b32_e32 v55, 0xffff0000, v46
	v_mul_f32_e32 v66, v14, v66
	v_mul_f32_e32 v67, v15, v67
	s_waitcnt vmcnt(56)
	v_lshlrev_b32_e32 v174, 16, v166
	v_mul_f32_e32 v54, v66, v54
	v_mul_f32_e32 v55, v67, v55
	v_mul_f32_e32 v66, v176, v64
	v_mul_f32_e32 v67, v177, v64
	v_and_b32_e32 v175, 0xffff0000, v166
	s_waitcnt vmcnt(52)
	v_lshlrev_b32_e32 v176, 16, v172
	v_and_b32_e32 v177, 0xffff0000, v172
	v_lshlrev_b32_e32 v166, 16, v167
	v_and_b32_e32 v167, 0xffff0000, v167
	v_lshlrev_b32_e32 v172, 16, v173
	v_and_b32_e32 v173, 0xffff0000, v173
	v_add_f32_e32 v174, v174, v176
	v_add_f32_e32 v175, v175, v177
	v_add_f32_e32 v172, v166, v172
	v_add_f32_e32 v173, v167, v173
	v_lshlrev_b32_e32 v166, 16, v134
	v_and_b32_e32 v167, 0xffff0000, v134
	s_waitcnt vmcnt(51)
	v_lshlrev_b32_e32 v176, 16, v136
	v_and_b32_e32 v177, 0xffff0000, v136
	global_store_dwordx2 v[80:81], v[60:61], off offset:1024
	v_mul_f32_e32 v60, v118, v64
	v_mul_f32_e32 v61, v119, v64
	v_add_f32_e32 v166, v166, v176
	v_add_f32_e32 v167, v167, v177
	v_lshlrev_b32_e32 v134, 16, v135
	v_and_b32_e32 v135, 0xffff0000, v135
	v_lshlrev_b32_e32 v136, 16, v137
	v_and_b32_e32 v137, 0xffff0000, v137
	v_lshlrev_b32_e32 v46, 16, v47
	v_and_b32_e32 v47, 0xffff0000, v47
	v_mul_f32_e32 v60, v16, v60
	v_mul_f32_e32 v61, v17, v61
	v_add_f32_e32 v134, v134, v136
	v_add_f32_e32 v135, v135, v137
	v_mov_b32_e32 v176, v175
	v_mov_b32_e32 v177, v167
	v_mul_f32_e32 v46, v60, v46
	v_mul_f32_e32 v47, v61, v47
	v_mul_f32_e32 v60, v178, v64
	v_mul_f32_e32 v61, v179, v64
	v_mov_b32_e32 v136, v174
	v_mov_b32_e32 v137, v166
	v_mul_f32_e32 v176, v176, v176
	v_mul_f32_e32 v177, v177, v177
	v_mov_b32_e32 v178, v173
	v_mov_b32_e32 v179, v135
	v_fma_f32 v136, v136, v136, v176
	v_fma_f32 v137, v137, v137, v177
	v_mov_b32_e32 v176, v172
	v_mov_b32_e32 v177, v134
	v_mul_f32_e32 v178, v178, v178
	v_mul_f32_e32 v179, v179, v179
	v_cvt_pk_bf16_f32 v54, v54, v55
	v_cvt_pk_bf16_f32 v55, v46, v47
	v_fma_f32 v176, v176, v176, v178
	v_fma_f32 v177, v177, v177, v179
	global_store_dwordx2 v[80:81], v[54:55], off offset:1536
	v_lshlrev_b32_e32 v46, 16, v122
	v_and_b32_e32 v47, 0xffff0000, v122
	v_lshlrev_b32_e32 v54, 16, v123
	v_and_b32_e32 v55, 0xffff0000, v123
	v_mul_f32_e32 v66, v18, v66
	v_mul_f32_e32 v67, v19, v67
	v_mul_f32_e32 v60, v20, v60
	v_mul_f32_e32 v61, v21, v61
	v_add_f32_e32 v136, v136, v176
	v_add_f32_e32 v137, v137, v177
	v_lshlrev_b32_e32 v176, 16, v128
	v_and_b32_e32 v177, 0xffff0000, v128
	s_waitcnt vmcnt(52)
	v_lshlrev_b32_e32 v178, 16, v130
	v_and_b32_e32 v179, 0xffff0000, v130
	v_lshlrev_b32_e32 v128, 16, v129
	v_and_b32_e32 v129, 0xffff0000, v129
	v_lshlrev_b32_e32 v130, 16, v131
	v_and_b32_e32 v131, 0xffff0000, v131
	v_mul_f32_e32 v54, v60, v54
	v_mul_f32_e32 v55, v61, v55
	v_mul_f32_e32 v46, v66, v46
	v_mul_f32_e32 v47, v67, v47
	v_add_f32_e32 v176, v176, v178
	v_add_f32_e32 v177, v177, v179
	v_add_f32_e32 v130, v128, v130
	v_add_f32_e32 v131, v129, v131
	v_cvt_pk_bf16_f32 v46, v46, v47
	v_cvt_pk_bf16_f32 v47, v54, v55
	v_mul_f32_e32 v60, v180, v64
	v_mul_f32_e32 v61, v181, v64
	v_mul_f32_e32 v66, v120, v64
	v_mul_f32_e32 v67, v121, v64
	v_mov_b32_e32 v178, v177
	v_mov_b32_e32 v179, v131
	global_store_dwordx2 v[80:81], v[46:47], off offset:2048
	v_lshlrev_b32_e32 v46, 16, v110
	v_and_b32_e32 v47, 0xffff0000, v110
	v_lshlrev_b32_e32 v54, 16, v111
	v_and_b32_e32 v55, 0xffff0000, v111
	v_mul_f32_e32 v66, v22, v66
	v_mul_f32_e32 v67, v23, v67
	v_mul_f32_e32 v60, v24, v60
	v_mul_f32_e32 v61, v25, v61
	v_mov_b32_e32 v128, v176
	v_mov_b32_e32 v129, v130
	v_mul_f32_e32 v178, v178, v178
	v_mul_f32_e32 v179, v179, v179
	v_mul_f32_e32 v54, v60, v54
	v_mul_f32_e32 v55, v61, v55
	v_mul_f32_e32 v46, v66, v46
	v_mul_f32_e32 v47, v67, v47
	v_mul_f32_e32 v60, v188, v64
	v_mul_f32_e32 v61, v189, v64
	v_fma_f32 v128, v128, v128, v178
	v_fma_f32 v129, v129, v129, v179
	v_cvt_pk_bf16_f32 v46, v46, v47
	v_cvt_pk_bf16_f32 v47, v54, v55
	v_lshlrev_b32_e32 v54, 16, v95
	v_and_b32_e32 v55, 0xffff0000, v95
	v_mul_f32_e32 v60, v28, v60
	v_mul_f32_e32 v61, v29, v61
	v_add_f32_e32 v178, v128, v129
	v_add_f32_e32 v179, v129, v128
	v_lshlrev_b32_e32 v128, 16, v112
	v_and_b32_e32 v129, 0xffff0000, v112
	s_waitcnt vmcnt(52)
; template <int CTRL> __device__ __forceinline__ float dpp_mov(float v) { return __builtin_bit_cast(float, __builtin_amdgcn_update_dpp(0, __builtin_bit_cast(int, v), CTRL, 0xF, 0xF, true)); }
; __device__ __forceinline__ float wave_sum(float v) {
;     v += dpp_mov<0xB1>(v);
;     v += dpp_mov<0x4E>(v);
;     v += dpp_mov<0x141>(v);
;     v += dpp_mov<0x140>(v);
;     const int iv = __builtin_bit_cast(int, v);
;     const float a = __builtin_bit_cast(float, __builtin_amdgcn_readlane(iv, 0)), b = __builtin_bit_cast(float, __builtin_amdgcn_readlane(iv, 16));
;     const float c = __builtin_bit_cast(float, __builtin_amdgcn_readlane(iv, 32)), d = __builtin_bit_cast(float, __builtin_amdgcn_readlane(iv, 48));
;     return (a + b) + (c + d);
; }
	v_lshlrev_b32_e32 v180, 16, v114
	v_and_b32_e32 v181, 0xffff0000, v114
	v_lshlrev_b32_e32 v112, 16, v113
	v_and_b32_e32 v113, 0xffff0000, v113
	v_lshlrev_b32_e32 v114, 16, v115
	v_and_b32_e32 v115, 0xffff0000, v115
	v_mul_f32_e32 v66, v184, v64
	v_mul_f32_e32 v67, v185, v64
	v_mul_f32_e32 v54, v60, v54
	v_mul_f32_e32 v55, v61, v55
	v_mul_f32_e32 v60, v186, v64
	v_mul_f32_e32 v61, v187, v64
	v_add_f32_e32 v128, v128, v180
	v_add_f32_e32 v129, v129, v181
	v_add_f32_e32 v112, v112, v114
	v_add_f32_e32 v113, v113, v115
	s_waitcnt vmcnt(47)
	v_lshlrev_b32_e32 v184, 16, v102
	v_and_b32_e32 v185, 0xffff0000, v102
	s_waitcnt vmcnt(43)
	v_lshlrev_b32_e32 v186, 16, v164
	v_and_b32_e32 v187, 0xffff0000, v164
	v_lshlrev_b32_e32 v102, 16, v103
	v_and_b32_e32 v103, 0xffff0000, v103
	v_lshlrev_b32_e32 v164, 16, v165
	v_and_b32_e32 v165, 0xffff0000, v165
	v_mul_f32_e32 v114, v129, v129
	v_mul_f32_e32 v180, v113, v113
	v_add_f32_e32 v184, v184, v186
	v_add_f32_e32 v185, v185, v187
	v_add_f32_e32 v164, v102, v164
	v_add_f32_e32 v165, v103, v165
	v_pk_add_f32 v[136:137], v[136:137], v[136:137] op_sel:[0,1] op_sel_hi:[1,0]
	v_fma_f32 v115, v129, v129, v114
	v_fma_f32 v114, v128, v128, v114
	v_fma_f32 v181, v113, v113, v180
	v_fma_f32 v180, v112, v112, v180
	v_mul_f32_e32 v102, v184, v184
	v_mul_f32_e32 v103, v185, v185
	v_mul_f32_e32 v186, v164, v164
	v_mul_f32_e32 v187, v165, v165
	v_mov_b32_e32 v137, v102
	v_mov_b32_e32 v179, v103
	v_mov_b32_e32 v115, v186
	v_mov_b32_e32 v181, v187
	v_add_f32_e32 v102, v136, v178
	v_add_f32_e32 v103, v137, v179
	v_add_f32_e32 v114, v114, v180
	v_add_f32_e32 v115, v115, v181
	s_waitcnt vmcnt(42)
	v_lshlrev_b32_e32 v136, 16, v160
	v_add_f32_e32 v102, v102, v114
	v_add_f32_e32 v103, v103, v115
	v_lshlrev_b32_e32 v114, 16, v84
	v_and_b32_e32 v115, 0xffff0000, v84
	v_and_b32_e32 v137, 0xffff0000, v160
	v_add_f32_e32 v114, v114, v136
	v_add_f32_e32 v115, v115, v137
	v_lshlrev_b32_e32 v84, 16, v85
	v_and_b32_e32 v85, 0xffff0000, v85
	v_lshlrev_b32_e32 v136, 16, v161
	v_and_b32_e32 v137, 0xffff0000, v161
	v_add_f32_e32 v178, v84, v136
	v_add_f32_e32 v179, v85, v137
	v_mov_b32_e32 v136, v115
	v_mov_b32_e32 v137, v179
	v_mov_b32_e32 v84, v114
	v_mov_b32_e32 v85, v178
	v_mul_f32_e32 v136, v136, v136
	v_mul_f32_e32 v137, v137, v137
	s_waitcnt vmcnt(41)
	v_lshlrev_b32_e32 v160, 16, v156
	v_fma_f32 v84, v84, v84, v136
	v_fma_f32 v85, v85, v85, v137
	v_lshlrev_b32_e32 v136, 16, v78
	v_and_b32_e32 v137, 0xffff0000, v78
	v_and_b32_e32 v161, 0xffff0000, v156
	v_add_f32_e32 v180, v136, v160
	v_add_f32_e32 v181, v137, v161
	v_lshlrev_b32_e32 v78, 16, v79
	v_and_b32_e32 v79, 0xffff0000, v79
	v_lshlrev_b32_e32 v136, 16, v157
	v_and_b32_e32 v137, 0xffff0000, v157
	v_add_f32_e32 v186, v78, v136
	v_add_f32_e32 v187, v79, v137
	v_lshlrev_b32_e32 v156, 16, v70
	v_and_b32_e32 v157, 0xffff0000, v70
	s_waitcnt vmcnt(40)
	v_lshlrev_b32_e32 v160, 16, v152
	v_and_b32_e32 v161, 0xffff0000, v152
	v_lshlrev_b32_e32 v70, 16, v71
	v_and_b32_e32 v71, 0xffff0000, v71
	v_lshlrev_b32_e32 v152, 16, v153
	v_and_b32_e32 v153, 0xffff0000, v153
	v_mul_f32_e32 v65, v191, v64
	v_mul_f32_e32 v64, v190, v64
	v_mul_f32_e32 v78, v181, v181
	v_mul_f32_e32 v136, v187, v187
	v_add_f32_e32 v188, v156, v160
	v_add_f32_e32 v189, v157, v161
	v_add_f32_e32 v190, v70, v152
	v_add_f32_e32 v191, v71, v153
	v_pk_add_f32 v[102:103], v[102:103], v[102:103] op_sel:[0,1] op_sel_hi:[1,0]
	v_pk_add_f32 v[84:85], v[84:85], v[84:85] op_sel:[0,1] op_sel_hi:[1,0]
	v_fma_f32 v79, v181, v181, v78
	v_fma_f32 v78, v180, v180, v78
	v_fma_f32 v137, v187, v187, v136
	v_fma_f32 v136, v186, v186, v136
	v_mul_f32_e32 v70, v188, v188
	v_mul_f32_e32 v71, v189, v189
	v_mul_f32_e32 v152, v190, v190
	v_mul_f32_e32 v153, v191, v191
	v_mov_b32_e32 v103, v70
	v_mov_b32_e32 v85, v71
	v_mov_b32_e32 v79, v152
	v_mov_b32_e32 v137, v153
	v_add_f32_e32 v70, v102, v84
	v_add_f32_e32 v71, v103, v85
	v_add_f32_e32 v78, v78, v136
	v_add_f32_e32 v79, v79, v137
	global_store_dwordx2 v[80:81], v[46:47], off offset:2560
	v_add_f32_e32 v70, v70, v78
	v_add_f32_e32 v71, v71, v79
	v_lshlrev_b32_e32 v46, 16, v94
	v_add_f32_e32 v70, v70, v71
	v_and_b32_e32 v47, 0xffff0000, v94
	v_mul_f32_e32 v66, v26, v66
	v_mul_f32_e32 v67, v27, v67
	v_add_f32_dpp v70, v70, v70 quad_perm:[1,0,3,2] row_mask:0xf bank_mask:0xf bound_ctrl:1
	v_mul_f32_e32 v46, v66, v46
	v_mul_f32_e32 v47, v67, v47
	v_mul_f32_e32 v64, v30, v64
	v_mul_f32_e32 v65, v31, v65
	v_add_f32_dpp v70, v70, v70 quad_perm:[2,3,0,1] row_mask:0xf bank_mask:0xf bound_ctrl:1
	v_cvt_pk_bf16_f32 v46, v46, v47
	v_cvt_pk_bf16_f32 v47, v54, v55
	v_add_f32_dpp v70, v70, v70 row_half_mirror row_mask:0xf bank_mask:0xf bound_ctrl:1
	global_store_dwordx2 v[80:81], v[46:47], off offset:3072
	v_lshlrev_b32_e32 v46, 16, v88
	v_add_f32_dpp v70, v70, v70 row_mirror row_mask:0xf bank_mask:0xf bound_ctrl:1
	v_and_b32_e32 v47, 0xffff0000, v88
	v_readlane_b32 s8, v70, 16
	v_readlane_b32 s9, v70, 48
	v_readlane_b32 s6, v70, 0
	v_readlane_b32 s7, v70, 32
	v_mov_b32_e32 v70, s8
	v_mov_b32_e32 v71, s9
	v_add_f32_e32 v70, s6, v70
	v_add_f32_e32 v71, s7, v71
	v_lshlrev_b32_e32 v54, 16, v89
	v_add_f32_e32 v70, v70, v71
	v_fmamk_f32 v70, v70, 0x3a000000, v252
	v_mul_f32_e32 v71, 0x4f800000, v70
	v_cmp_gt_f32_e32 vcc, s55, v70
	v_and_b32_e32 v55, 0xffff0000, v89
	v_mul_f32_e32 v60, v32, v60
	v_mul_f32_e32 v61, v33, v61
	v_cndmask_b32_e32 v70, v70, v71, vcc
	v_sqrt_f32_e32 v71, v70
	s_add_i32 s18, s10, 0x3800
	v_mul_f32_e32 v54, v60, v54
	v_mul_f32_e32 v55, v61, v55
	v_mul_f32_e32 v46, v64, v46
	v_mul_f32_e32 v47, v65, v47
	v_add_u32_e32 v78, -1, v71
	v_fma_f32 v79, -v78, v71, v70
	v_cmp_ge_f32_e64 s[8:9], 0, v79
; template <bool HG>
; __device__ __forceinline__ void readout_phase2(const Args& a, Frame& F, const float* gain, int nrows) {
;     ...
;     const bool cx = ML + nw < nrows;
;     RO_LOAD(f2, b2, g2, cx ? ML + nw : nw + 7 * 2048);
	v_add_u32_e32 v79, 1, v71
	s_ashr_i32 s19, s18, 31
	v_cndmask_b32_e64 v78, v71, v78, s[8:9]
	v_fma_f32 v71, -v79, v71, v70
	v_cvt_pk_bf16_f32 v46, v46, v47
	v_cvt_pk_bf16_f32 v47, v54, v55
	s_lshl_b64 s[16:17], s[18:19], 12
	v_cmp_lt_f32_e64 s[8:9], 0, v71
	global_store_dwordx2 v[80:81], v[46:47], off offset:3584
	v_lshl_add_u64 v[46:47], v[36:37], 0, s[16:17]
	v_cndmask_b32_e64 v71, v78, v79, s[8:9]
	v_lshl_add_u64 v[66:67], v[46:47], 0, v[0:1]
	v_lshl_add_u64 v[46:47], v[38:39], 0, s[16:17]
	v_mul_f32_e32 v78, 0x37800000, v71
	global_store_dwordx2 v[80:81], v[170:171], off
	v_lshl_add_u64 v[170:171], v[46:47], 0, v[0:1]
	v_lshl_add_u64 v[46:47], v[40:41], 0, s[16:17]
	v_cndmask_b32_e32 v71, v71, v78, vcc
	v_cmp_class_f32_e32 vcc, v70, v253
	v_lshl_add_u64 v[168:169], v[46:47], 0, v[0:1]
	global_load_dwordx2 v[144:145], v[66:67], off nt
	global_load_dwordx2 v[138:139], v[66:67], off offset:512 nt
	global_load_dwordx2 v[120:121], v[66:67], off offset:1024 nt
	global_load_dwordx2 v[110:111], v[66:67], off offset:1536 nt
	global_load_dwordx2 v[146:147], v[170:171], off nt
	global_load_dwordx2 v[142:143], v[170:171], off offset:512 nt
	global_load_dwordx2 v[122:123], v[170:171], off offset:1024 nt
	global_load_dwordx2 v[118:119], v[170:171], off offset:1536 nt
	global_load_dwordx2 v[64:65], v[168:169], off nt
	global_load_dwordx2 v[60:61], v[168:169], off offset:512 nt
	global_load_dwordx2 v[54:55], v[168:169], off offset:1024 nt
	global_load_dwordx2 v[46:47], v[168:169], off offset:1536 nt
	global_load_dwordx2 v[94:95], v[66:67], off offset:2048 nt
	global_load_dwordx2 v[88:89], v[66:67], off offset:2560 nt
	global_load_dwordx2 v[80:81], v[66:67], off offset:3072 nt
	s_nop 0
	global_load_dwordx2 v[66:67], v[66:67], off offset:3584 nt
	s_nop 0
	global_load_dwordx2 v[160:161], v[170:171], off offset:2048 nt
	global_load_dwordx2 v[156:157], v[170:171], off offset:2560 nt
	global_load_dwordx2 v[152:153], v[170:171], off offset:3072 nt
	global_load_dwordx2 v[136:137], v[170:171], off offset:3584 nt
	v_cndmask_b32_e32 v170, v71, v70, vcc
	v_div_scale_f32 v171, s[6:7], v170, v170, 1.0
	v_rcp_f32_e32 v192, v171
	global_load_dwordx2 v[102:103], v[168:169], off offset:2048 nt
	global_load_dwordx2 v[84:85], v[168:169], off offset:2560 nt
	global_load_dwordx2 v[78:79], v[168:169], off offset:3072 nt
	global_load_dwordx2 v[70:71], v[168:169], off offset:3584 nt
	s_addk_i32 s10, 0x4000
	s_cmp_lt_i32 s10, s47
	v_fma_f32 v168, -v171, v192, 1.0
	v_fmac_f32_e32 v192, v168, v192
	v_div_scale_f32 v168, vcc, 1.0, v170, 1.0
	v_mul_f32_e32 v169, v168, v192
	v_fma_f32 v193, -v171, v169, v168
	v_fmac_f32_e32 v169, v193, v192
	v_fma_f32 v168, -v171, v169, v168
	v_div_fmas_f32 v168, v168, v192, v169
	v_div_fixup_f32 v168, v168, v170, 1.0
	v_mul_f32_e32 v172, v172, v168
	v_mul_f32_e32 v173, v173, v168
	v_mul_f32_e32 v174, v174, v168
	v_mul_f32_e32 v175, v175, v168
	v_lshlrev_b32_e32 v192, 16, v62
	v_and_b32_e32 v193, 0xffff0000, v62
	v_lshlrev_b32_e32 v62, 16, v63
	v_and_b32_e32 v63, 0xffff0000, v63
	v_mul_f32_e32 v174, v2, v174
	v_mul_f32_e32 v175, v3, v175
	v_mul_f32_e32 v172, v4, v172
	v_mul_f32_e32 v173, v5, v173
	v_mul_f32_e32 v134, v134, v168
	v_mul_f32_e32 v135, v135, v168
	v_mul_f32_e32 v62, v172, v62
	v_mul_f32_e32 v63, v173, v63
	v_mul_f32_e32 v172, v174, v192
	v_mul_f32_e32 v173, v175, v193
	v_mul_f32_e32 v166, v166, v168
	v_mul_f32_e32 v167, v167, v168
	v_cvt_pk_bf16_f32 v172, v172, v173
	v_cvt_pk_bf16_f32 v173, v62, v63
	v_lshlrev_b32_e32 v62, 16, v56
	v_and_b32_e32 v63, 0xffff0000, v56
	v_lshlrev_b32_e32 v56, 16, v57
	v_and_b32_e32 v57, 0xffff0000, v57
	v_mul_f32_e32 v166, v6, v166
	v_mul_f32_e32 v167, v7, v167
	v_mul_f32_e32 v134, v8, v134
	v_mul_f32_e32 v135, v9, v135
	v_lshl_add_u64 v[170:171], v[34:35], 0, s[14:15]
	v_mul_f32_e32 v56, v134, v56
	v_mul_f32_e32 v57, v135, v57
	v_mul_f32_e32 v62, v166, v62
	v_mul_f32_e32 v63, v167, v63
	v_lshl_add_u64 v[170:171], v[170:171], 0, v[0:1]
	v_cvt_pk_bf16_f32 v62, v62, v63
	v_cvt_pk_bf16_f32 v63, v56, v57
	global_store_dwordx2 v[170:171], v[62:63], off offset:512
	v_mul_f32_e32 v62, v130, v168
	v_mul_f32_e32 v63, v131, v168
	v_mul_f32_e32 v130, v176, v168
	v_mul_f32_e32 v131, v177, v168
	v_lshlrev_b32_e32 v56, 16, v50
	v_and_b32_e32 v57, 0xffff0000, v50
	v_lshlrev_b32_e32 v50, 16, v51
	v_and_b32_e32 v51, 0xffff0000, v51
	v_mul_f32_e32 v130, v10, v130
	v_mul_f32_e32 v131, v11, v131
	v_mul_f32_e32 v62, v12, v62
	v_mul_f32_e32 v63, v13, v63
	v_mul_f32_e32 v56, v130, v56
	v_mul_f32_e32 v57, v131, v57
	v_mul_f32_e32 v50, v62, v50
	v_mul_f32_e32 v51, v63, v51
	v_cvt_pk_bf16_f32 v56, v56, v57
	v_cvt_pk_bf16_f32 v57, v50, v51
	global_store_dwordx2 v[170:171], v[56:57], off offset:1024
	v_mul_f32_e32 v56, v112, v168
	v_mul_f32_e32 v57, v113, v168
	v_mul_f32_e32 v62, v128, v168
	v_mul_f32_e32 v63, v129, v168
	v_lshlrev_b32_e32 v50, 16, v44
	v_and_b32_e32 v51, 0xffff0000, v44
	v_lshlrev_b32_e32 v44, 16, v45
	v_and_b32_e32 v45, 0xffff0000, v45
	v_mul_f32_e32 v62, v14, v62
	v_mul_f32_e32 v63, v15, v63
	v_mul_f32_e32 v56, v16, v56
	v_mul_f32_e32 v57, v17, v57
	v_mul_f32_e32 v50, v62, v50
	v_mul_f32_e32 v51, v63, v51
	v_mul_f32_e32 v44, v56, v44
	v_mul_f32_e32 v45, v57, v45
	v_cvt_pk_bf16_f32 v50, v50, v51
	v_cvt_pk_bf16_f32 v51, v44, v45
	v_mul_f32_e32 v56, v164, v168
	v_mul_f32_e32 v57, v165, v168
	v_mul_f32_e32 v62, v184, v168
	v_mul_f32_e32 v63, v185, v168
	global_store_dwordx2 v[170:171], v[50:51], off offset:1536
	s_waitcnt vmcnt(62)
	v_lshlrev_b32_e32 v44, 16, v116
	v_and_b32_e32 v45, 0xffff0000, v116
	v_lshlrev_b32_e32 v50, 16, v117
	v_and_b32_e32 v51, 0xffff0000, v117
	v_mul_f32_e32 v62, v18, v62
	v_mul_f32_e32 v63, v19, v63
	v_mul_f32_e32 v56, v20, v56
	v_mul_f32_e32 v57, v21, v57
	v_mul_f32_e32 v44, v62, v44
	v_mul_f32_e32 v45, v63, v45
	v_mul_f32_e32 v50, v56, v50
	v_mul_f32_e32 v51, v57, v51
	v_cvt_pk_bf16_f32 v44, v44, v45
	v_cvt_pk_bf16_f32 v45, v50, v51
	v_mul_f32_e32 v56, v178, v168
	v_mul_f32_e32 v57, v179, v168
	v_mul_f32_e32 v62, v114, v168
	v_mul_f32_e32 v63, v115, v168
	global_store_dwordx2 v[170:171], v[44:45], off offset:2048
	v_lshlrev_b32_e32 v44, 16, v104
	v_and_b32_e32 v45, 0xffff0000, v104
	v_lshlrev_b32_e32 v50, 16, v105
	v_and_b32_e32 v51, 0xffff0000, v105
	v_mul_f32_e32 v62, v22, v62
	v_mul_f32_e32 v63, v23, v63
	v_mul_f32_e32 v56, v24, v56
	v_mul_f32_e32 v57, v25, v57
	v_mul_f32_e32 v44, v62, v44
	v_mul_f32_e32 v45, v63, v45
	v_mul_f32_e32 v50, v56, v50
	v_mul_f32_e32 v51, v57, v51
	v_cvt_pk_bf16_f32 v44, v44, v45
	v_cvt_pk_bf16_f32 v45, v50, v51
	v_mul_f32_e32 v56, v186, v168
	v_mul_f32_e32 v57, v187, v168
	v_mul_f32_e32 v62, v180, v168
	v_mul_f32_e32 v63, v181, v168
	global_store_dwordx2 v[170:171], v[44:45], off offset:2560
	v_lshlrev_b32_e32 v44, 16, v92
	v_and_b32_e32 v45, 0xffff0000, v92
	v_lshlrev_b32_e32 v50, 16, v93
	v_and_b32_e32 v51, 0xffff0000, v93
	v_mul_f32_e32 v62, v26, v62
	v_mul_f32_e32 v63, v27, v63
	v_mul_f32_e32 v56, v28, v56
	v_mul_f32_e32 v57, v29, v57
	v_mul_f32_e32 v44, v62, v44
	v_mul_f32_e32 v45, v63, v45
	v_mul_f32_e32 v50, v56, v50
	v_mul_f32_e32 v51, v57, v51
	v_cvt_pk_bf16_f32 v44, v44, v45
	v_cvt_pk_bf16_f32 v45, v50, v51
	v_mul_f32_e32 v56, v190, v168
	v_mul_f32_e32 v57, v191, v168
	v_mul_f32_e32 v62, v188, v168
	v_mul_f32_e32 v63, v189, v168
	global_store_dwordx2 v[170:171], v[44:45], off offset:3072
	v_lshlrev_b32_e32 v44, 16, v86
	v_and_b32_e32 v45, 0xffff0000, v86
	v_lshlrev_b32_e32 v50, 16, v87
	v_and_b32_e32 v51, 0xffff0000, v87
	v_mul_f32_e32 v62, v30, v62
	v_mul_f32_e32 v63, v31, v63
	v_mul_f32_e32 v56, v32, v56
	v_mul_f32_e32 v57, v33, v57
	v_mul_f32_e32 v44, v62, v44
	v_mul_f32_e32 v45, v63, v45
	v_mul_f32_e32 v50, v56, v50
	v_mul_f32_e32 v51, v57, v51
	v_cvt_pk_bf16_f32 v44, v44, v45
	v_cvt_pk_bf16_f32 v45, v50, v51
	global_store_dwordx2 v[170:171], v[172:173], off
	global_store_dwordx2 v[170:171], v[44:45], off offset:3584
	s_waitcnt vmcnt(62)
	v_lshlrev_b32_e32 v168, 16, v140
	v_and_b32_e32 v169, 0xffff0000, v140
	s_waitcnt vmcnt(59)
	v_lshlrev_b32_e32 v170, 16, v148
	v_and_b32_e32 v171, 0xffff0000, v148
	v_lshlrev_b32_e32 v140, 16, v141
	v_and_b32_e32 v141, 0xffff0000, v141
	v_lshlrev_b32_e32 v148, 16, v149
	v_and_b32_e32 v149, 0xffff0000, v149
	v_add_f32_e32 v168, v168, v170
	v_add_f32_e32 v169, v169, v171
	v_add_f32_e32 v148, v140, v148
	v_add_f32_e32 v149, v141, v149
	v_lshlrev_b32_e32 v140, 16, v126
	v_and_b32_e32 v141, 0xffff0000, v126
	s_waitcnt vmcnt(58)
	v_lshlrev_b32_e32 v170, 16, v132
	v_and_b32_e32 v171, 0xffff0000, v132
	v_add_f32_e32 v140, v140, v170
	v_add_f32_e32 v141, v141, v171
	v_lshlrev_b32_e32 v126, 16, v127
	v_and_b32_e32 v127, 0xffff0000, v127
	v_lshlrev_b32_e32 v132, 16, v133
	v_and_b32_e32 v133, 0xffff0000, v133
	v_add_f32_e32 v132, v126, v132
	v_add_f32_e32 v133, v127, v133
	v_mov_b32_e32 v170, v169
	v_mov_b32_e32 v171, v141
	v_mov_b32_e32 v126, v168
	v_mov_b32_e32 v127, v140
	v_mul_f32_e32 v170, v170, v170
	v_mul_f32_e32 v171, v171, v171
	v_mov_b32_e32 v172, v149
	v_mov_b32_e32 v173, v133
	v_fma_f32 v126, v126, v126, v170
	v_fma_f32 v127, v127, v127, v171
	v_mov_b32_e32 v170, v148
	v_mov_b32_e32 v171, v132
	v_mul_f32_e32 v172, v172, v172
	v_mul_f32_e32 v173, v173, v173
	s_waitcnt vmcnt(47)
	v_lshlrev_b32_e32 v178, 16, v162
	v_fma_f32 v170, v170, v170, v172
	v_fma_f32 v171, v171, v171, v173
	v_lshlrev_b32_e32 v172, 16, v124
	v_add_f32_e32 v126, v126, v170
	v_add_f32_e32 v127, v127, v171
	v_lshlrev_b32_e32 v170, 16, v108
	v_and_b32_e32 v171, 0xffff0000, v108
	v_and_b32_e32 v173, 0xffff0000, v124
	v_lshlrev_b32_e32 v108, 16, v109
	v_and_b32_e32 v109, 0xffff0000, v109
	v_lshlrev_b32_e32 v124, 16, v125
	v_and_b32_e32 v125, 0xffff0000, v125
	v_add_f32_e32 v170, v170, v172
	v_add_f32_e32 v171, v171, v173
	v_add_f32_e32 v174, v108, v124
	v_add_f32_e32 v175, v109, v125
	v_mov_b32_e32 v124, v171
	v_mov_b32_e32 v125, v175
	v_mov_b32_e32 v108, v170
	v_mov_b32_e32 v109, v174
	v_mul_f32_e32 v124, v124, v124
	v_mul_f32_e32 v125, v125, v125
	v_lshlrev_b32_e32 v172, 16, v100
	v_fma_f32 v108, v108, v108, v124
	v_fma_f32 v109, v109, v109, v125
	v_lshlrev_b32_e32 v124, 16, v98
	v_and_b32_e32 v125, 0xffff0000, v98
	v_and_b32_e32 v173, 0xffff0000, v100
	v_add_f32_e32 v172, v124, v172
	v_add_f32_e32 v173, v125, v173
	v_lshlrev_b32_e32 v98, 16, v99
	v_and_b32_e32 v99, 0xffff0000, v99
	v_lshlrev_b32_e32 v100, 16, v101
	v_and_b32_e32 v101, 0xffff0000, v101
	v_lshlrev_b32_e32 v124, 16, v90
	v_and_b32_e32 v125, 0xffff0000, v90
	v_and_b32_e32 v179, 0xffff0000, v162
	v_add_f32_e32 v176, v98, v100
	v_add_f32_e32 v177, v99, v101
	v_add_f32_e32 v178, v124, v178
	v_add_f32_e32 v179, v125, v179
	v_lshlrev_b32_e32 v90, 16, v91
	v_and_b32_e32 v91, 0xffff0000, v91
	v_lshlrev_b32_e32 v124, 16, v163
	v_and_b32_e32 v125, 0xffff0000, v163
	v_mul_f32_e32 v98, v173, v173
	v_mul_f32_e32 v100, v177, v177
	v_add_f32_e32 v162, v90, v124
	v_add_f32_e32 v163, v91, v125
	v_pk_add_f32 v[126:127], v[126:127], v[126:127] op_sel:[0,1] op_sel_hi:[1,0]
	v_pk_add_f32 v[108:109], v[108:109], v[108:109] op_sel:[0,1] op_sel_hi:[1,0]
	v_fma_f32 v99, v173, v173, v98
	v_fma_f32 v98, v172, v172, v98
	v_fma_f32 v101, v177, v177, v100
	v_fma_f32 v100, v176, v176, v100
	v_mul_f32_e32 v90, v178, v178
	v_mul_f32_e32 v91, v179, v179
	v_mul_f32_e32 v124, v162, v162
	v_mul_f32_e32 v125, v163, v163
	v_mov_b32_e32 v127, v90
	v_mov_b32_e32 v109, v91
	v_mov_b32_e32 v99, v124
	v_mov_b32_e32 v101, v125
	v_add_f32_e32 v90, v126, v108
	v_add_f32_e32 v91, v127, v109
	v_add_f32_e32 v98, v98, v100
	v_add_f32_e32 v99, v99, v101
	s_waitcnt vmcnt(46)
; template <bool HG>
; __device__ __forceinline__ void readout_phase2(const Args& a, Frame& F, const float* gain, int nrows) {
;     ...
;     const bool cx = ML + nw < nrows;
;     RO_LOAD(f2, b2, g2, cx ? ML + nw : nw + 7 * 2048);
	v_lshlrev_b32_e32 v100, 16, v158
	v_add_f32_e32 v90, v90, v98
	v_add_f32_e32 v91, v91, v99
	v_lshlrev_b32_e32 v98, 16, v76
	v_and_b32_e32 v99, 0xffff0000, v76
	v_and_b32_e32 v101, 0xffff0000, v158
	v_add_f32_e32 v180, v98, v100
	v_add_f32_e32 v181, v99, v101
	v_lshlrev_b32_e32 v76, 16, v77
	v_and_b32_e32 v77, 0xffff0000, v77
	v_lshlrev_b32_e32 v98, 16, v159
	v_and_b32_e32 v99, 0xffff0000, v159
	v_add_f32_e32 v158, v76, v98
	v_add_f32_e32 v159, v77, v99
	v_mov_b32_e32 v98, v181
	v_mov_b32_e32 v99, v159
	v_mov_b32_e32 v76, v180
	v_mov_b32_e32 v77, v158
	v_mul_f32_e32 v98, v98, v98
	v_mul_f32_e32 v99, v99, v99
	s_waitcnt vmcnt(45)
	v_lshlrev_b32_e32 v100, 16, v154
	v_fma_f32 v76, v76, v76, v98
	v_fma_f32 v77, v77, v77, v99
	v_lshlrev_b32_e32 v98, 16, v74
	v_and_b32_e32 v99, 0xffff0000, v74
	v_and_b32_e32 v101, 0xffff0000, v154
	v_add_f32_e32 v184, v98, v100
	v_add_f32_e32 v185, v99, v101
	v_lshlrev_b32_e32 v74, 16, v75
	v_and_b32_e32 v75, 0xffff0000, v75
	v_lshlrev_b32_e32 v98, 16, v155
	v_and_b32_e32 v99, 0xffff0000, v155
	v_lshlrev_b32_e32 v100, 16, v68
	v_and_b32_e32 v101, 0xffff0000, v68
	s_waitcnt vmcnt(44)
	v_lshlrev_b32_e32 v108, 16, v150
	v_and_b32_e32 v109, 0xffff0000, v150
	v_add_f32_e32 v154, v74, v98
	v_add_f32_e32 v155, v75, v99
	v_add_f32_e32 v186, v100, v108
	v_add_f32_e32 v187, v101, v109
	v_lshlrev_b32_e32 v68, 16, v69
	v_and_b32_e32 v69, 0xffff0000, v69
	v_lshlrev_b32_e32 v100, 16, v151
	v_and_b32_e32 v101, 0xffff0000, v151
	v_mul_f32_e32 v74, v185, v185
	v_mul_f32_e32 v98, v155, v155
	v_add_f32_e32 v150, v68, v100
	v_add_f32_e32 v151, v69, v101
	v_pk_add_f32 v[90:91], v[90:91], v[90:91] op_sel:[0,1] op_sel_hi:[1,0]
	v_pk_add_f32 v[76:77], v[76:77], v[76:77] op_sel:[0,1] op_sel_hi:[1,0]
	v_fma_f32 v75, v185, v185, v74
	v_fma_f32 v74, v184, v184, v74
	v_fma_f32 v99, v155, v155, v98
	v_fma_f32 v98, v154, v154, v98
	v_mul_f32_e32 v68, v186, v186
	v_mul_f32_e32 v69, v187, v187
	v_mul_f32_e32 v100, v150, v150
	v_mul_f32_e32 v101, v151, v151
	v_mov_b32_e32 v91, v68
	v_mov_b32_e32 v77, v69
	v_mov_b32_e32 v75, v100
	v_mov_b32_e32 v99, v101
	v_add_f32_e32 v68, v90, v76
	v_add_f32_e32 v69, v91, v77
	v_add_f32_e32 v74, v74, v98
	v_add_f32_e32 v75, v75, v99
	s_cselect_b64 s[14:15], -1, 0
	v_add_f32_e32 v68, v68, v74
	v_add_f32_e32 v69, v69, v75
	s_and_b64 s[6:7], s[14:15], exec
	v_add_f32_e32 v68, v68, v69
	s_cselect_b32 s6, s10, s18
	s_ashr_i32 s7, s6, 31
	v_add_f32_dpp v68, v68, v68 quad_perm:[1,0,3,2] row_mask:0xf bank_mask:0xf bound_ctrl:1
	s_lshl_b64 s[6:7], s[6:7], 12
	v_lshl_add_u64 v[36:37], v[36:37], 0, s[6:7]
	v_add_f32_dpp v68, v68, v68 quad_perm:[2,3,0,1] row_mask:0xf bank_mask:0xf bound_ctrl:1
	v_lshl_add_u64 v[50:51], v[36:37], 0, v[0:1]
	v_lshl_add_u64 v[36:37], v[38:39], 0, s[6:7]
	v_add_f32_dpp v68, v68, v68 row_half_mirror row_mask:0xf bank_mask:0xf bound_ctrl:1
	v_lshl_add_u64 v[166:167], v[36:37], 0, v[0:1]
	v_lshl_add_u64 v[36:37], v[40:41], 0, s[6:7]
	v_add_f32_dpp v68, v68, v68 row_mirror row_mask:0xf bank_mask:0xf bound_ctrl:1
	v_lshl_add_u64 v[164:165], v[36:37], 0, v[0:1]
	v_readlane_b32 s8, v68, 16
	v_readlane_b32 s9, v68, 48
	v_readlane_b32 s6, v68, 0
	v_readlane_b32 s7, v68, 32
	v_mov_b32_e32 v68, s8
	v_mov_b32_e32 v69, s9
	v_add_f32_e32 v68, s6, v68
	v_add_f32_e32 v69, s7, v69
	global_load_dwordx2 v[130:131], v[50:51], off nt
	global_load_dwordx2 v[116:117], v[50:51], off offset:512 nt
	global_load_dwordx2 v[112:113], v[50:51], off offset:1024 nt
	global_load_dwordx2 v[92:93], v[50:51], off offset:1536 nt
	global_load_dwordx2 v[134:135], v[166:167], off nt
	global_load_dwordx2 v[128:129], v[166:167], off offset:512 nt
	global_load_dwordx2 v[114:115], v[166:167], off offset:1024 nt
	global_load_dwordx2 v[104:105], v[166:167], off offset:1536 nt
	global_load_dwordx2 v[44:45], v[164:165], off nt
	global_load_dwordx2 v[40:41], v[164:165], off offset:512 nt
	global_load_dwordx2 v[38:39], v[164:165], off offset:1024 nt
	global_load_dwordx2 v[36:37], v[164:165], off offset:1536 nt
	global_load_dwordx2 v[86:87], v[50:51], off offset:2048 nt
	global_load_dwordx2 v[62:63], v[50:51], off offset:2560 nt
	global_load_dwordx2 v[56:57], v[50:51], off offset:3072 nt
	s_nop 0
	global_load_dwordx2 v[50:51], v[50:51], off offset:3584 nt
	v_add_f32_e32 v68, v68, v69
	v_fmamk_f32 v68, v68, 0x3a000000, v252
	v_mul_f32_e32 v69, 0x4f800000, v68
	v_cmp_gt_f32_e32 vcc, s55, v68
	global_load_dwordx2 v[124:125], v[166:167], off offset:2048 nt
	global_load_dwordx2 v[108:109], v[166:167], off offset:2560 nt
	global_load_dwordx2 v[100:101], v[166:167], off offset:3072 nt
	global_load_dwordx2 v[98:99], v[166:167], off offset:3584 nt
	v_cndmask_b32_e32 v68, v68, v69, vcc
	v_sqrt_f32_e32 v69, v68
	s_nop 0
	v_add_u32_e32 v74, -1, v69
	v_fma_f32 v75, -v74, v69, v68
	v_cmp_ge_f32_e64 s[8:9], 0, v75
	v_add_u32_e32 v75, 1, v69
	s_nop 0
	v_cndmask_b32_e64 v74, v69, v74, s[8:9]
	v_fma_f32 v69, -v75, v69, v68
	v_cmp_lt_f32_e64 s[8:9], 0, v69
	s_nop 1
	v_cndmask_b32_e64 v69, v74, v75, s[8:9]
	v_mul_f32_e32 v74, 0x37800000, v69
	v_cndmask_b32_e32 v69, v69, v74, vcc
	v_cmp_class_f32_e32 vcc, v68, v253
	s_nop 1
	v_cndmask_b32_e32 v126, v69, v68, vcc
	v_div_scale_f32 v127, s[6:7], v126, v126, 1.0
	v_rcp_f32_e32 v166, v127
	global_load_dwordx2 v[90:91], v[164:165], off offset:2048 nt
	global_load_dwordx2 v[76:77], v[164:165], off offset:2560 nt
	global_load_dwordx2 v[74:75], v[164:165], off offset:3072 nt
	global_load_dwordx2 v[68:69], v[164:165], off offset:3584 nt
	v_fma_f32 v164, -v127, v166, 1.0
	v_fmac_f32_e32 v166, v164, v166
	v_div_scale_f32 v164, vcc, 1.0, v126, 1.0
	v_mul_f32_e32 v165, v164, v166
	v_fma_f32 v167, -v127, v165, v164
	v_fmac_f32_e32 v165, v167, v166
	v_fma_f32 v127, -v127, v165, v164
	v_div_fmas_f32 v127, v127, v166, v165
	v_div_fixup_f32 v164, v127, v126, 1.0
	v_mul_f32_e32 v148, v148, v164
	v_mul_f32_e32 v149, v149, v164
	v_mul_f32_e32 v168, v168, v164
	v_mul_f32_e32 v169, v169, v164
	v_lshlrev_b32_e32 v166, 16, v58
	v_and_b32_e32 v167, 0xffff0000, v58
	v_lshlrev_b32_e32 v58, 16, v59
	v_and_b32_e32 v59, 0xffff0000, v59
	v_mul_f32_e32 v168, v2, v168
	v_mul_f32_e32 v169, v3, v169
	v_mul_f32_e32 v148, v4, v148
	v_mul_f32_e32 v149, v5, v149
	v_mul_f32_e32 v132, v132, v164
	v_mul_f32_e32 v133, v133, v164
	v_mul_f32_e32 v58, v148, v58
	v_mul_f32_e32 v59, v149, v59
	v_mul_f32_e32 v148, v168, v166
	v_mul_f32_e32 v149, v169, v167
	v_mul_f32_e32 v140, v140, v164
	v_mul_f32_e32 v141, v141, v164
	v_cvt_pk_bf16_f32 v148, v148, v149
	v_cvt_pk_bf16_f32 v149, v58, v59
	v_lshlrev_b32_e32 v58, 16, v52
	v_and_b32_e32 v59, 0xffff0000, v52
	v_lshlrev_b32_e32 v52, 16, v53
	v_and_b32_e32 v53, 0xffff0000, v53
	v_mul_f32_e32 v140, v6, v140
	v_mul_f32_e32 v141, v7, v141
	v_mul_f32_e32 v132, v8, v132
	v_mul_f32_e32 v133, v9, v133
	v_lshl_add_u64 v[126:127], v[34:35], 0, s[12:13]
	v_mul_f32_e32 v52, v132, v52
	v_mul_f32_e32 v53, v133, v53
	v_mul_f32_e32 v58, v140, v58
	v_mul_f32_e32 v59, v141, v59
	v_lshl_add_u64 v[126:127], v[126:127], 0, v[0:1]
	v_cvt_pk_bf16_f32 v58, v58, v59
	v_cvt_pk_bf16_f32 v59, v52, v53
	global_store_dwordx2 v[126:127], v[58:59], off offset:512
	v_mul_f32_e32 v58, v174, v164
	v_mul_f32_e32 v59, v175, v164
	v_mul_f32_e32 v132, v170, v164
	v_mul_f32_e32 v133, v171, v164
	v_lshlrev_b32_e32 v52, 16, v48
	v_and_b32_e32 v53, 0xffff0000, v48
	v_lshlrev_b32_e32 v48, 16, v49
	v_and_b32_e32 v49, 0xffff0000, v49
	v_mul_f32_e32 v132, v10, v132
	v_mul_f32_e32 v133, v11, v133
	v_mul_f32_e32 v58, v12, v58
	v_mul_f32_e32 v59, v13, v59
	v_mul_f32_e32 v52, v132, v52
	v_mul_f32_e32 v53, v133, v53
	v_mul_f32_e32 v48, v58, v48
	v_mul_f32_e32 v49, v59, v49
	v_cvt_pk_bf16_f32 v52, v52, v53
	v_cvt_pk_bf16_f32 v53, v48, v49
	global_store_dwordx2 v[126:127], v[52:53], off offset:1024
	v_mul_f32_e32 v52, v176, v164
	v_mul_f32_e32 v53, v177, v164
	v_mul_f32_e32 v58, v172, v164
	v_mul_f32_e32 v59, v173, v164
	v_lshlrev_b32_e32 v48, 16, v42
	v_and_b32_e32 v49, 0xffff0000, v42
	v_lshlrev_b32_e32 v42, 16, v43
	v_and_b32_e32 v43, 0xffff0000, v43
	v_mul_f32_e32 v58, v14, v58
	v_mul_f32_e32 v59, v15, v59
	v_mul_f32_e32 v52, v16, v52
	v_mul_f32_e32 v53, v17, v53
	v_mul_f32_e32 v48, v58, v48
	v_mul_f32_e32 v49, v59, v49
	v_mul_f32_e32 v42, v52, v42
	v_mul_f32_e32 v43, v53, v43
	v_cvt_pk_bf16_f32 v48, v48, v49
	v_cvt_pk_bf16_f32 v49, v42, v43
	v_mul_f32_e32 v52, v162, v164
	v_mul_f32_e32 v53, v163, v164
	v_mul_f32_e32 v58, v178, v164
	v_mul_f32_e32 v59, v179, v164
	global_store_dwordx2 v[126:127], v[48:49], off offset:1536
	s_waitcnt vmcnt(62)
	v_lshlrev_b32_e32 v42, 16, v106
	v_and_b32_e32 v43, 0xffff0000, v106
	v_lshlrev_b32_e32 v48, 16, v107
	v_and_b32_e32 v49, 0xffff0000, v107
	v_mul_f32_e32 v58, v18, v58
	v_mul_f32_e32 v59, v19, v59
	v_mul_f32_e32 v52, v20, v52
	v_mul_f32_e32 v53, v21, v53
	v_mul_f32_e32 v42, v58, v42
	v_mul_f32_e32 v43, v59, v43
	v_mul_f32_e32 v48, v52, v48
	v_mul_f32_e32 v49, v53, v49
	v_cvt_pk_bf16_f32 v42, v42, v43
	v_cvt_pk_bf16_f32 v43, v48, v49
	v_mul_f32_e32 v52, v158, v164
	v_mul_f32_e32 v53, v159, v164
	v_mul_f32_e32 v58, v180, v164
	v_mul_f32_e32 v59, v181, v164
	global_store_dwordx2 v[126:127], v[42:43], off offset:2048
	v_lshlrev_b32_e32 v42, 16, v96
	v_and_b32_e32 v43, 0xffff0000, v96
	v_lshlrev_b32_e32 v48, 16, v97
	v_and_b32_e32 v49, 0xffff0000, v97
	v_mul_f32_e32 v58, v22, v58
	v_mul_f32_e32 v59, v23, v59
	v_mul_f32_e32 v52, v24, v52
	v_mul_f32_e32 v53, v25, v53
	v_mul_f32_e32 v42, v58, v42
	v_mul_f32_e32 v43, v59, v43
	v_mul_f32_e32 v48, v52, v48
	v_mul_f32_e32 v49, v53, v49
	v_cvt_pk_bf16_f32 v42, v42, v43
	v_cvt_pk_bf16_f32 v43, v48, v49
	v_mul_f32_e32 v52, v154, v164
	v_mul_f32_e32 v53, v155, v164
	v_mul_f32_e32 v58, v184, v164
	v_mul_f32_e32 v59, v185, v164
	global_store_dwordx2 v[126:127], v[42:43], off offset:2560
	v_lshlrev_b32_e32 v42, 16, v82
	v_and_b32_e32 v43, 0xffff0000, v82
	v_lshlrev_b32_e32 v48, 16, v83
	v_and_b32_e32 v49, 0xffff0000, v83
	v_mul_f32_e32 v58, v26, v58
	v_mul_f32_e32 v59, v27, v59
	v_mul_f32_e32 v52, v28, v52
	v_mul_f32_e32 v53, v29, v53
	v_mul_f32_e32 v42, v58, v42
	v_mul_f32_e32 v43, v59, v43
	v_mul_f32_e32 v48, v52, v48
	v_mul_f32_e32 v49, v53, v49
	v_cvt_pk_bf16_f32 v42, v42, v43
	v_cvt_pk_bf16_f32 v43, v48, v49
	global_store_dwordx2 v[126:127], v[42:43], off offset:3072
	v_mul_f32_e32 v42, v186, v164
	v_mul_f32_e32 v43, v187, v164
	s_waitcnt vmcnt(57)
	v_lshlrev_b32_e32 v48, 16, v146
	v_mul_f32_e32 v132, v30, v42
	v_mul_f32_e32 v133, v31, v43
	v_lshlrev_b32_e32 v42, 16, v144
	v_and_b32_e32 v43, 0xffff0000, v144
	v_and_b32_e32 v49, 0xffff0000, v146
	v_add_f32_e32 v48, v42, v48
	v_add_f32_e32 v49, v43, v49
	v_lshlrev_b32_e32 v42, 16, v145
	v_and_b32_e32 v43, 0xffff0000, v145
	v_lshlrev_b32_e32 v52, 16, v147
	v_and_b32_e32 v53, 0xffff0000, v147
	v_add_f32_e32 v58, v42, v52
	v_add_f32_e32 v59, v43, v53
	v_lshlrev_b32_e32 v42, 16, v138
	v_and_b32_e32 v43, 0xffff0000, v138
	s_waitcnt vmcnt(56)
	v_lshlrev_b32_e32 v52, 16, v142
	v_and_b32_e32 v53, 0xffff0000, v142
	v_add_f32_e32 v42, v42, v52
	v_add_f32_e32 v43, v43, v53
	v_lshlrev_b32_e32 v52, 16, v139
	v_and_b32_e32 v53, 0xffff0000, v139
	v_lshlrev_b32_e32 v96, 16, v143
	v_and_b32_e32 v97, 0xffff0000, v143
	v_add_f32_e32 v52, v52, v96
	v_add_f32_e32 v53, v53, v97
	v_mov_b32_e32 v138, v49
	v_mov_b32_e32 v139, v43
	v_mov_b32_e32 v96, v48
	v_mov_b32_e32 v97, v42
	v_mul_f32_e32 v138, v138, v138
	v_mul_f32_e32 v139, v139, v139
	v_mov_b32_e32 v140, v59
	v_mov_b32_e32 v141, v53
	v_fma_f32 v96, v96, v96, v138
	v_fma_f32 v97, v97, v97, v139
	v_mov_b32_e32 v138, v58
	v_mov_b32_e32 v139, v52
	v_mul_f32_e32 v140, v140, v140
	v_mul_f32_e32 v141, v141, v141
	s_waitcnt vmcnt(54)
	v_lshlrev_b32_e32 v142, 16, v118
	v_fma_f32 v138, v138, v138, v140
	v_fma_f32 v139, v139, v139, v141
	v_lshlrev_b32_e32 v140, 16, v122
	v_add_f32_e32 v96, v96, v138
	v_add_f32_e32 v97, v97, v139
	v_and_b32_e32 v141, 0xffff0000, v122
	v_add_f32_e32 v138, v96, v97
	v_add_f32_e32 v139, v97, v96
	v_lshlrev_b32_e32 v96, 16, v120
	v_and_b32_e32 v97, 0xffff0000, v120
	v_lshlrev_b32_e32 v120, 16, v121
	v_and_b32_e32 v121, 0xffff0000, v121
	v_lshlrev_b32_e32 v122, 16, v123
	v_and_b32_e32 v123, 0xffff0000, v123
	v_add_f32_e32 v96, v96, v140
	v_add_f32_e32 v97, v97, v141
	v_add_f32_e32 v120, v120, v122
	v_add_f32_e32 v121, v121, v123
	v_mov_b32_e32 v140, v97
	v_mov_b32_e32 v141, v121
	v_mov_b32_e32 v122, v96
	v_mov_b32_e32 v123, v120
	v_mul_f32_e32 v140, v140, v140
	v_mul_f32_e32 v141, v141, v141
	v_and_b32_e32 v143, 0xffff0000, v118
	v_fma_f32 v122, v122, v122, v140
	v_fma_f32 v123, v123, v123, v141
	v_lshlrev_b32_e32 v140, 16, v110
	v_and_b32_e32 v141, 0xffff0000, v110
	v_lshlrev_b32_e32 v110, 16, v111
	v_and_b32_e32 v111, 0xffff0000, v111
	v_lshlrev_b32_e32 v118, 16, v119
	v_and_b32_e32 v119, 0xffff0000, v119
	s_waitcnt vmcnt(49)
	v_lshlrev_b32_e32 v144, 16, v94
	v_and_b32_e32 v145, 0xffff0000, v94
	s_waitcnt vmcnt(45)
	v_lshlrev_b32_e32 v146, 16, v160
	v_and_b32_e32 v147, 0xffff0000, v160
	v_add_f32_e32 v140, v140, v142
	v_add_f32_e32 v141, v141, v143
	v_add_f32_e32 v110, v110, v118
	v_add_f32_e32 v111, v111, v119
	v_add_f32_e32 v144, v144, v146
	v_add_f32_e32 v145, v145, v147
	v_lshlrev_b32_e32 v94, 16, v95
	v_and_b32_e32 v95, 0xffff0000, v95
	v_lshlrev_b32_e32 v146, 16, v161
	v_and_b32_e32 v147, 0xffff0000, v161
	v_mul_f32_e32 v118, v141, v141
	v_mul_f32_e32 v142, v111, v111
	v_add_f32_e32 v94, v94, v146
	v_add_f32_e32 v95, v95, v147
	global_store_dwordx2 v[126:127], v[148:149], off
	v_pk_add_f32 v[122:123], v[122:123], v[122:123] op_sel:[0,1] op_sel_hi:[1,0]
	v_fma_f32 v119, v141, v141, v118
	v_fma_f32 v118, v140, v140, v118
	v_fma_f32 v143, v111, v111, v142
	v_fma_f32 v142, v110, v110, v142
	v_mul_f32_e32 v146, v144, v144
	v_mul_f32_e32 v147, v145, v145
	v_mul_f32_e32 v148, v94, v94
	v_mul_f32_e32 v149, v95, v95
	v_mov_b32_e32 v139, v146
	v_mov_b32_e32 v123, v147
	v_mov_b32_e32 v119, v148
	v_mov_b32_e32 v143, v149
	v_add_f32_e32 v122, v138, v122
	v_add_f32_e32 v123, v139, v123
	v_add_f32_e32 v118, v118, v142
	v_add_f32_e32 v119, v119, v143
	s_waitcnt vmcnt(45)
	v_lshlrev_b32_e32 v138, 16, v156
	v_add_f32_e32 v118, v122, v118
	v_add_f32_e32 v119, v123, v119
	v_lshlrev_b32_e32 v122, 16, v88
	v_and_b32_e32 v123, 0xffff0000, v88
	v_and_b32_e32 v139, 0xffff0000, v156
	v_add_f32_e32 v122, v122, v138
	v_add_f32_e32 v123, v123, v139
	v_lshlrev_b32_e32 v88, 16, v89
	v_and_b32_e32 v89, 0xffff0000, v89
	v_lshlrev_b32_e32 v138, 16, v157
	v_and_b32_e32 v139, 0xffff0000, v157
	v_add_f32_e32 v88, v88, v138
	v_add_f32_e32 v89, v89, v139
	v_mov_b32_e32 v142, v123
	v_mov_b32_e32 v143, v89
	v_mov_b32_e32 v138, v122
	v_mov_b32_e32 v139, v88
	v_mul_f32_e32 v142, v142, v142
	v_mul_f32_e32 v143, v143, v143
	s_waitcnt vmcnt(44)
	v_lshlrev_b32_e32 v146, 16, v152
	v_fma_f32 v138, v138, v138, v142
	v_fma_f32 v139, v139, v139, v143
	v_lshlrev_b32_e32 v142, 16, v80
	v_and_b32_e32 v143, 0xffff0000, v80
	v_and_b32_e32 v147, 0xffff0000, v152
	v_add_f32_e32 v142, v142, v146
	v_add_f32_e32 v143, v143, v147
	v_lshlrev_b32_e32 v80, 16, v81
	v_and_b32_e32 v81, 0xffff0000, v81
	v_lshlrev_b32_e32 v146, 16, v153
	v_and_b32_e32 v147, 0xffff0000, v153
	v_mul_f32_e32 v106, v150, v164
	v_mul_f32_e32 v107, v151, v164
	v_add_f32_e32 v80, v80, v146
	v_add_f32_e32 v81, v81, v147
	v_lshlrev_b32_e32 v150, 16, v66
	v_and_b32_e32 v151, 0xffff0000, v66
	s_waitcnt vmcnt(43)
	v_lshlrev_b32_e32 v152, 16, v136
	v_and_b32_e32 v153, 0xffff0000, v136
	v_lshlrev_b32_e32 v66, 16, v67
	v_and_b32_e32 v67, 0xffff0000, v67
	v_lshlrev_b32_e32 v136, 16, v137
	v_and_b32_e32 v137, 0xffff0000, v137
	v_mul_f32_e32 v146, v143, v143
	v_mul_f32_e32 v148, v81, v81
	v_add_f32_e32 v150, v150, v152
	v_add_f32_e32 v151, v151, v153
	v_add_f32_e32 v66, v66, v136
	v_add_f32_e32 v67, v67, v137
	v_pk_add_f32 v[118:119], v[118:119], v[118:119] op_sel:[0,1] op_sel_hi:[1,0]
	v_pk_add_f32 v[138:139], v[138:139], v[138:139] op_sel:[0,1] op_sel_hi:[1,0]
	v_fma_f32 v147, v143, v143, v146
	v_fma_f32 v146, v142, v142, v146
	v_fma_f32 v149, v81, v81, v148
	v_fma_f32 v148, v80, v80, v148
	v_mul_f32_e32 v136, v150, v150
	v_mul_f32_e32 v137, v151, v151
	v_mul_f32_e32 v152, v66, v66
	v_mul_f32_e32 v153, v67, v67
	v_mov_b32_e32 v119, v136
	v_mov_b32_e32 v139, v137
	v_mov_b32_e32 v147, v152
	v_mov_b32_e32 v149, v153
	v_add_f32_e32 v118, v118, v138
	v_add_f32_e32 v119, v119, v139
	v_add_f32_e32 v136, v146, v148
	v_add_f32_e32 v137, v147, v149
	v_lshlrev_b32_e32 v82, 16, v72
	v_add_f32_e32 v118, v118, v136
	v_add_f32_e32 v119, v119, v137
	v_and_b32_e32 v83, 0xffff0000, v72
	v_add_f32_e32 v118, v118, v119
	v_lshlrev_b32_e32 v72, 16, v73
	v_and_b32_e32 v73, 0xffff0000, v73
	v_add_f32_dpp v118, v118, v118 quad_perm:[1,0,3,2] row_mask:0xf bank_mask:0xf bound_ctrl:1
	v_mul_f32_e32 v106, v32, v106
	v_mul_f32_e32 v107, v33, v107
	v_mul_f32_e32 v82, v132, v82
	v_mul_f32_e32 v83, v133, v83
	v_add_f32_dpp v118, v118, v118 quad_perm:[2,3,0,1] row_mask:0xf bank_mask:0xf bound_ctrl:1
	v_mul_f32_e32 v72, v106, v72
	v_mul_f32_e32 v73, v107, v73
	v_cvt_pk_bf16_f32 v82, v82, v83
	v_add_f32_dpp v118, v118, v118 row_half_mirror row_mask:0xf bank_mask:0xf bound_ctrl:1
	v_cvt_pk_bf16_f32 v83, v72, v73
	global_store_dwordx2 v[126:127], v[82:83], off offset:3584
	v_add_f32_dpp v118, v118, v118 row_mirror row_mask:0xf bank_mask:0xf bound_ctrl:1
	s_nop 0
; template <int CTRL> __device__ __forceinline__ float dpp_mov(float v) { return __builtin_bit_cast(float, __builtin_amdgcn_update_dpp(0, __builtin_bit_cast(int, v), CTRL, 0xF, 0xF, true)); }
; __device__ __forceinline__ float wave_sum(float v) {
;     v += dpp_mov<0xB1>(v);
;     v += dpp_mov<0x4E>(v);
;     v += dpp_mov<0x141>(v);
;     v += dpp_mov<0x140>(v);
;     const int iv = __builtin_bit_cast(int, v);
;     const float a = __builtin_bit_cast(float, __builtin_amdgcn_readlane(iv, 0)), b = __builtin_bit_cast(float, __builtin_amdgcn_readlane(iv, 16));
;     const float c = __builtin_bit_cast(float, __builtin_amdgcn_readlane(iv, 32)), d = __builtin_bit_cast(float, __builtin_amdgcn_readlane(iv, 48));
;     return (a + b) + (c + d);
; }
; template <bool HG>
; __device__ __forceinline__ void readout_phase2(const Args& a, Frame& F, const float* gain, int nrows) {
;     ...
;     if (cx) RO_FINISH(f2, b2, g2, ML + nw);
	v_readlane_b32 s8, v118, 16
	v_readlane_b32 s9, v118, 48
	v_readlane_b32 s6, v118, 0
	v_readlane_b32 s7, v118, 32
	v_mov_b32_e32 v118, s8
	v_mov_b32_e32 v119, s9
	v_add_f32_e32 v118, s6, v118
	v_add_f32_e32 v119, s7, v119
	s_nop 0
	v_add_f32_e32 v118, v118, v119
	v_fmamk_f32 v118, v118, 0x3a000000, v252
	v_mul_f32_e32 v119, 0x4f800000, v118
	v_cmp_gt_f32_e32 vcc, s55, v118
	s_nop 1
	v_cndmask_b32_e32 v118, v118, v119, vcc
	v_sqrt_f32_e32 v119, v118
	s_nop 0
	v_add_u32_e32 v106, -1, v119
	v_fma_f32 v107, -v106, v119, v118
	v_cmp_ge_f32_e64 s[8:9], 0, v107
	v_add_u32_e32 v107, 1, v119
	s_nop 0
	v_cndmask_b32_e64 v106, v119, v106, s[8:9]
	v_fma_f32 v119, -v107, v119, v118
	v_cmp_lt_f32_e64 s[8:9], 0, v119
	s_nop 1
	v_cndmask_b32_e64 v106, v106, v107, s[8:9]
	v_mul_f32_e32 v107, 0x37800000, v106
	v_cndmask_b32_e32 v106, v106, v107, vcc
	v_cmp_class_f32_e32 vcc, v118, v253
	s_nop 1
	v_cndmask_b32_e32 v106, v106, v118, vcc
	v_div_scale_f32 v107, s[6:7], v106, v106, 1.0
	v_rcp_f32_e32 v118, v107
	s_nop 0
	v_fma_f32 v72, -v107, v118, 1.0
	v_fmac_f32_e32 v118, v72, v118
	v_div_scale_f32 v72, vcc, 1.0, v106, 1.0
	v_mul_f32_e32 v73, v72, v118
	v_fma_f32 v82, -v107, v73, v72
	v_fmac_f32_e32 v73, v82, v118
	v_fma_f32 v72, -v107, v73, v72
	v_div_fmas_f32 v72, v72, v118, v73
	v_div_fixup_f32 v72, v72, v106, 1.0
	v_mul_f32_e32 v58, v58, v72
	v_mul_f32_e32 v59, v59, v72
	v_mul_f32_e32 v48, v48, v72
	v_mul_f32_e32 v49, v49, v72
	v_lshlrev_b32_e32 v106, 16, v64
	v_and_b32_e32 v107, 0xffff0000, v64
	v_lshlrev_b32_e32 v64, 16, v65
	v_and_b32_e32 v65, 0xffff0000, v65
	v_mul_f32_e32 v48, v2, v48
	v_mul_f32_e32 v49, v3, v49
	v_mul_f32_e32 v58, v4, v58
	v_mul_f32_e32 v59, v5, v59
	v_lshl_add_u64 v[82:83], v[34:35], 0, s[16:17]
	v_mul_f32_e32 v58, v58, v64
	v_mul_f32_e32 v59, v59, v65
	v_mul_f32_e32 v48, v48, v106
	v_mul_f32_e32 v49, v49, v107
	v_lshl_add_u64 v[82:83], v[82:83], 0, v[0:1]
	v_cvt_pk_bf16_f32 v48, v48, v49
	v_cvt_pk_bf16_f32 v49, v58, v59
	v_mul_f32_e32 v52, v52, v72
	v_mul_f32_e32 v53, v53, v72
	v_mul_f32_e32 v42, v42, v72
	v_mul_f32_e32 v43, v43, v72
	global_store_dwordx2 v[82:83], v[48:49], off
	v_lshlrev_b32_e32 v48, 16, v60
	v_and_b32_e32 v49, 0xffff0000, v60
	v_lshlrev_b32_e32 v58, 16, v61
	v_and_b32_e32 v59, 0xffff0000, v61
	v_mul_f32_e32 v42, v6, v42
	v_mul_f32_e32 v43, v7, v43
	v_mul_f32_e32 v52, v8, v52
	v_mul_f32_e32 v53, v9, v53
	v_mul_f32_e32 v42, v42, v48
	v_mul_f32_e32 v43, v43, v49
	v_mul_f32_e32 v52, v52, v58
	v_mul_f32_e32 v53, v53, v59
	v_cvt_pk_bf16_f32 v42, v42, v43
	v_cvt_pk_bf16_f32 v43, v52, v53
	global_store_dwordx2 v[82:83], v[42:43], off offset:512
	v_lshlrev_b32_e32 v42, 16, v54
	v_and_b32_e32 v43, 0xffff0000, v54
	v_lshlrev_b32_e32 v48, 16, v55
	v_and_b32_e32 v49, 0xffff0000, v55
	v_mul_f32_e32 v52, v120, v72
	v_mul_f32_e32 v53, v121, v72
	v_mul_f32_e32 v54, v96, v72
	v_mul_f32_e32 v55, v97, v72
	v_mul_f32_e32 v52, v12, v52
	v_mul_f32_e32 v53, v13, v53
	v_mul_f32_e32 v54, v10, v54
	v_mul_f32_e32 v55, v11, v55
	v_mul_f32_e32 v48, v52, v48
	v_mul_f32_e32 v49, v53, v49
	v_mul_f32_e32 v42, v54, v42
	v_mul_f32_e32 v43, v55, v43
	v_mul_f32_e32 v52, v140, v72
	v_mul_f32_e32 v53, v141, v72
	v_cvt_pk_bf16_f32 v42, v42, v43
	v_cvt_pk_bf16_f32 v43, v48, v49
	v_mul_f32_e32 v48, v110, v72
	v_mul_f32_e32 v49, v111, v72
	global_store_dwordx2 v[82:83], v[42:43], off offset:1024
	v_lshlrev_b32_e32 v42, 16, v46
	v_and_b32_e32 v43, 0xffff0000, v46
	v_lshlrev_b32_e32 v46, 16, v47
	v_and_b32_e32 v47, 0xffff0000, v47
	v_mul_f32_e32 v52, v14, v52
	v_mul_f32_e32 v53, v15, v53
	v_mul_f32_e32 v48, v16, v48
	v_mul_f32_e32 v49, v17, v49
	v_mul_f32_e32 v42, v52, v42
	v_mul_f32_e32 v43, v53, v43
	v_mul_f32_e32 v46, v48, v46
	v_mul_f32_e32 v47, v49, v47
	v_cvt_pk_bf16_f32 v42, v42, v43
	v_cvt_pk_bf16_f32 v43, v46, v47
	v_mul_f32_e32 v48, v94, v72
	v_mul_f32_e32 v49, v95, v72
	v_mul_f32_e32 v52, v144, v72
	v_mul_f32_e32 v53, v145, v72
	global_store_dwordx2 v[82:83], v[42:43], off offset:1536
	s_waitcnt vmcnt(47)
	v_lshlrev_b32_e32 v42, 16, v102
	v_and_b32_e32 v43, 0xffff0000, v102
	v_lshlrev_b32_e32 v46, 16, v103
	v_and_b32_e32 v47, 0xffff0000, v103
	v_mul_f32_e32 v52, v18, v52
	v_mul_f32_e32 v53, v19, v53
	v_mul_f32_e32 v48, v20, v48
	v_mul_f32_e32 v49, v21, v49
	v_mul_f32_e32 v42, v52, v42
	v_mul_f32_e32 v43, v53, v43
	v_mul_f32_e32 v46, v48, v46
	v_mul_f32_e32 v47, v49, v47
	v_cvt_pk_bf16_f32 v42, v42, v43
	v_cvt_pk_bf16_f32 v43, v46, v47
	v_mul_f32_e32 v48, v88, v72
	v_mul_f32_e32 v49, v89, v72
	v_mul_f32_e32 v52, v122, v72
	v_mul_f32_e32 v53, v123, v72
	global_store_dwordx2 v[82:83], v[42:43], off offset:2048
	s_waitcnt vmcnt(47)
	v_lshlrev_b32_e32 v42, 16, v84
	v_and_b32_e32 v43, 0xffff0000, v84
	v_lshlrev_b32_e32 v46, 16, v85
	v_and_b32_e32 v47, 0xffff0000, v85
	v_mul_f32_e32 v52, v22, v52
	v_mul_f32_e32 v53, v23, v53
	v_mul_f32_e32 v48, v24, v48
	v_mul_f32_e32 v49, v25, v49
	v_mul_f32_e32 v42, v52, v42
	v_mul_f32_e32 v43, v53, v43
	v_mul_f32_e32 v46, v48, v46
	v_mul_f32_e32 v47, v49, v47
	v_cvt_pk_bf16_f32 v42, v42, v43
	v_cvt_pk_bf16_f32 v43, v46, v47
	v_mul_f32_e32 v48, v80, v72
	v_mul_f32_e32 v49, v81, v72
	v_mul_f32_e32 v52, v142, v72
	v_mul_f32_e32 v53, v143, v72
	global_store_dwordx2 v[82:83], v[42:43], off offset:2560
	s_waitcnt vmcnt(47)
	v_lshlrev_b32_e32 v42, 16, v78
	v_and_b32_e32 v43, 0xffff0000, v78
	v_lshlrev_b32_e32 v46, 16, v79
	v_and_b32_e32 v47, 0xffff0000, v79
	v_mul_f32_e32 v52, v26, v52
	v_mul_f32_e32 v53, v27, v53
	v_mul_f32_e32 v48, v28, v48
	v_mul_f32_e32 v49, v29, v49
	v_mul_f32_e32 v42, v52, v42
	v_mul_f32_e32 v43, v53, v43
	v_mul_f32_e32 v46, v48, v46
	v_mul_f32_e32 v47, v49, v47
	v_cvt_pk_bf16_f32 v42, v42, v43
	v_cvt_pk_bf16_f32 v43, v46, v47
	v_mul_f32_e32 v48, v66, v72
	v_mul_f32_e32 v49, v67, v72
	v_mul_f32_e32 v52, v150, v72
	v_mul_f32_e32 v53, v151, v72
	global_store_dwordx2 v[82:83], v[42:43], off offset:3072
	s_waitcnt vmcnt(47)
	v_lshlrev_b32_e32 v42, 16, v70
	v_and_b32_e32 v43, 0xffff0000, v70
	v_lshlrev_b32_e32 v46, 16, v71
	v_and_b32_e32 v47, 0xffff0000, v71
	v_mul_f32_e32 v52, v30, v52
	v_mul_f32_e32 v53, v31, v53
	v_mul_f32_e32 v48, v32, v48
	v_mul_f32_e32 v49, v33, v49
	v_mul_f32_e32 v42, v52, v42
	v_mul_f32_e32 v43, v53, v43
	v_mul_f32_e32 v46, v48, v46
	v_mul_f32_e32 v47, v49, v47
	v_cvt_pk_bf16_f32 v42, v42, v43
	v_cvt_pk_bf16_f32 v43, v46, v47
	s_and_b64 vcc, exec, s[14:15]
	global_store_dwordx2 v[82:83], v[42:43], off offset:3584
	s_cbranch_vccz .LBB0_582
; template <bool HG>
; __device__ __forceinline__ void readout_phase2(const Args& a, Frame& F, const float* gain, int nrows) {
;     ...
;     if (cx) RO_FINISH(f2, b2, g2, ML + nw);
	s_waitcnt vmcnt(39)
	v_lshlrev_b32_e32 v42, 16, v130
	v_and_b32_e32 v43, 0xffff0000, v130
	s_waitcnt vmcnt(35)
	v_lshlrev_b32_e32 v46, 16, v134
	v_and_b32_e32 v47, 0xffff0000, v134
	v_add_f32_e32 v46, v42, v46
	v_add_f32_e32 v47, v43, v47
	v_lshlrev_b32_e32 v42, 16, v131
	v_and_b32_e32 v43, 0xffff0000, v131
	v_lshlrev_b32_e32 v48, 16, v135
	v_and_b32_e32 v49, 0xffff0000, v135
	v_add_f32_e32 v52, v42, v48
	v_add_f32_e32 v53, v43, v49
	v_lshlrev_b32_e32 v42, 16, v116
	v_and_b32_e32 v43, 0xffff0000, v116
	s_waitcnt vmcnt(34)
	v_lshlrev_b32_e32 v48, 16, v128
	v_and_b32_e32 v49, 0xffff0000, v128
	v_add_f32_e32 v42, v42, v48
	v_add_f32_e32 v43, v43, v49
	v_lshlrev_b32_e32 v48, 16, v117
	v_and_b32_e32 v49, 0xffff0000, v117
	v_lshlrev_b32_e32 v54, 16, v129
	v_and_b32_e32 v55, 0xffff0000, v129
	v_add_f32_e32 v48, v48, v54
	v_add_f32_e32 v49, v49, v55
	v_mov_b32_e32 v58, v47
	v_mov_b32_e32 v59, v43
	v_mov_b32_e32 v54, v46
	v_mov_b32_e32 v55, v42
	v_mul_f32_e32 v58, v58, v58
	v_mul_f32_e32 v59, v59, v59
	v_mov_b32_e32 v60, v53
	v_mov_b32_e32 v61, v49
	v_fma_f32 v54, v54, v54, v58
	v_fma_f32 v55, v55, v55, v59
	v_mov_b32_e32 v58, v52
	v_mov_b32_e32 v59, v48
	v_mul_f32_e32 v60, v60, v60
	v_mul_f32_e32 v61, v61, v61
	s_waitcnt vmcnt(33)
	v_lshlrev_b32_e32 v64, 16, v115
	v_fma_f32 v58, v58, v58, v60
	v_fma_f32 v59, v59, v59, v61
	v_lshlrev_b32_e32 v60, 16, v114
	v_add_f32_e32 v54, v54, v58
	v_add_f32_e32 v55, v55, v59
	v_and_b32_e32 v61, 0xffff0000, v114
	v_add_f32_e32 v58, v54, v55
	v_add_f32_e32 v59, v55, v54
	v_lshlrev_b32_e32 v54, 16, v112
	v_and_b32_e32 v55, 0xffff0000, v112
	v_add_f32_e32 v54, v54, v60
	v_add_f32_e32 v55, v55, v61
	v_lshlrev_b32_e32 v60, 16, v113
	v_and_b32_e32 v61, 0xffff0000, v113
	v_and_b32_e32 v65, 0xffff0000, v115
	v_add_f32_e32 v60, v60, v64
	v_add_f32_e32 v61, v61, v65
	v_mov_b32_e32 v66, v55
	v_mov_b32_e32 v67, v61
	v_mov_b32_e32 v64, v54
	v_mov_b32_e32 v65, v60
	v_mul_f32_e32 v66, v66, v66
	v_mul_f32_e32 v67, v67, v67
	s_waitcnt vmcnt(32)
	v_lshlrev_b32_e32 v70, 16, v104
	v_fma_f32 v64, v64, v64, v66
	v_fma_f32 v65, v65, v65, v67
	v_lshlrev_b32_e32 v66, 16, v92
	v_and_b32_e32 v67, 0xffff0000, v92
	v_and_b32_e32 v71, 0xffff0000, v104
	v_add_f32_e32 v66, v66, v70
	v_add_f32_e32 v67, v67, v71
	v_lshlrev_b32_e32 v70, 16, v93
	v_and_b32_e32 v71, 0xffff0000, v93
	v_lshlrev_b32_e32 v72, 16, v105
	v_and_b32_e32 v73, 0xffff0000, v105
	s_waitcnt vmcnt(27)
	v_lshlrev_b32_e32 v80, 16, v86
	v_and_b32_e32 v81, 0xffff0000, v86
	s_waitcnt vmcnt(23)
	v_lshlrev_b32_e32 v82, 16, v124
	v_and_b32_e32 v83, 0xffff0000, v124
	v_add_f32_e32 v70, v70, v72
	v_add_f32_e32 v71, v71, v73
	v_add_f32_e32 v80, v80, v82
	v_add_f32_e32 v81, v81, v83
	v_lshlrev_b32_e32 v82, 16, v87
	v_and_b32_e32 v83, 0xffff0000, v87
	v_lshlrev_b32_e32 v84, 16, v125
	v_and_b32_e32 v85, 0xffff0000, v125
	v_mul_f32_e32 v72, v67, v67
	v_mul_f32_e32 v78, v71, v71
	v_add_f32_e32 v82, v82, v84
	v_add_f32_e32 v83, v83, v85
	v_pk_add_f32 v[64:65], v[64:65], v[64:65] op_sel:[0,1] op_sel_hi:[1,0]
	v_fma_f32 v73, v67, v67, v72
	v_fma_f32 v72, v66, v66, v72
	v_fma_f32 v79, v71, v71, v78
	v_fma_f32 v78, v70, v70, v78
	v_mul_f32_e32 v84, v80, v80
	v_mul_f32_e32 v85, v81, v81
	v_mul_f32_e32 v86, v82, v82
	v_mul_f32_e32 v87, v83, v83
	v_mov_b32_e32 v59, v84
	v_mov_b32_e32 v65, v85
	v_mov_b32_e32 v73, v86
	v_mov_b32_e32 v79, v87
	v_add_f32_e32 v58, v58, v64
	v_add_f32_e32 v59, v59, v65
	v_add_f32_e32 v64, v72, v78
	v_add_f32_e32 v65, v73, v79
	s_waitcnt vmcnt(22)
	v_lshlrev_b32_e32 v72, 16, v108
	v_add_f32_e32 v58, v58, v64
	v_add_f32_e32 v59, v59, v65
	v_lshlrev_b32_e32 v64, 16, v62
	v_and_b32_e32 v65, 0xffff0000, v62
	v_and_b32_e32 v73, 0xffff0000, v108
	v_add_f32_e32 v64, v64, v72
	v_add_f32_e32 v65, v65, v73
	v_lshlrev_b32_e32 v62, 16, v63
	v_and_b32_e32 v63, 0xffff0000, v63
	v_lshlrev_b32_e32 v72, 16, v109
	v_and_b32_e32 v73, 0xffff0000, v109
	v_add_f32_e32 v62, v62, v72
	v_add_f32_e32 v63, v63, v73
	v_mov_b32_e32 v78, v65
	v_mov_b32_e32 v79, v63
	v_mov_b32_e32 v72, v64
	v_mov_b32_e32 v73, v62
	v_mul_f32_e32 v78, v78, v78
	v_mul_f32_e32 v79, v79, v79
	s_waitcnt vmcnt(21)
	v_lshlrev_b32_e32 v84, 16, v100
	v_fma_f32 v72, v72, v72, v78
	v_fma_f32 v73, v73, v73, v79
	v_lshlrev_b32_e32 v78, 16, v56
	v_and_b32_e32 v79, 0xffff0000, v56
	v_and_b32_e32 v85, 0xffff0000, v100
	v_add_f32_e32 v78, v78, v84
	v_add_f32_e32 v79, v79, v85
	v_lshlrev_b32_e32 v56, 16, v57
	v_and_b32_e32 v57, 0xffff0000, v57
	v_lshlrev_b32_e32 v84, 16, v101
	v_and_b32_e32 v85, 0xffff0000, v101
	v_lshlrev_b32_e32 v88, 16, v50
	v_and_b32_e32 v89, 0xffff0000, v50
	s_waitcnt vmcnt(20)
; template <int CTRL> __device__ __forceinline__ float dpp_mov(float v) { return __builtin_bit_cast(float, __builtin_amdgcn_update_dpp(0, __builtin_bit_cast(int, v), CTRL, 0xF, 0xF, true)); }
; __device__ __forceinline__ float wave_sum(float v) {
;     v += dpp_mov<0xB1>(v);
;     v += dpp_mov<0x4E>(v);
;     v += dpp_mov<0x141>(v);
;     v += dpp_mov<0x140>(v);
;     const int iv = __builtin_bit_cast(int, v);
;     const float a = __builtin_bit_cast(float, __builtin_amdgcn_readlane(iv, 0)), b = __builtin_bit_cast(float, __builtin_amdgcn_readlane(iv, 16));
;     const float c = __builtin_bit_cast(float, __builtin_amdgcn_readlane(iv, 32)), d = __builtin_bit_cast(float, __builtin_amdgcn_readlane(iv, 48));
;     return (a + b) + (c + d);
; }
	v_lshlrev_b32_e32 v92, 16, v98
	v_and_b32_e32 v93, 0xffff0000, v98
	v_add_f32_e32 v56, v56, v84
	v_add_f32_e32 v57, v57, v85
	v_add_f32_e32 v88, v88, v92
	v_add_f32_e32 v89, v89, v93
	v_lshlrev_b32_e32 v50, 16, v51
	v_and_b32_e32 v51, 0xffff0000, v51
	v_lshlrev_b32_e32 v92, 16, v99
	v_and_b32_e32 v93, 0xffff0000, v99
	v_mul_f32_e32 v84, v79, v79
	v_mul_f32_e32 v86, v57, v57
	v_add_f32_e32 v50, v50, v92
	v_add_f32_e32 v51, v51, v93
	v_pk_add_f32 v[58:59], v[58:59], v[58:59] op_sel:[0,1] op_sel_hi:[1,0]
	v_pk_add_f32 v[72:73], v[72:73], v[72:73] op_sel:[0,1] op_sel_hi:[1,0]
	v_fma_f32 v85, v79, v79, v84
	v_fma_f32 v84, v78, v78, v84
	v_fma_f32 v87, v57, v57, v86
	v_fma_f32 v86, v56, v56, v86
	v_mul_f32_e32 v92, v88, v88
	v_mul_f32_e32 v93, v89, v89
	v_mul_f32_e32 v94, v50, v50
	v_mul_f32_e32 v95, v51, v51
	v_mov_b32_e32 v59, v92
	v_mov_b32_e32 v73, v93
	v_mov_b32_e32 v85, v94
	v_mov_b32_e32 v87, v95
	v_add_f32_e32 v58, v58, v72
	v_add_f32_e32 v59, v59, v73
	v_add_f32_e32 v72, v84, v86
	v_add_f32_e32 v73, v85, v87
	s_ashr_i32 s11, s10, 31
	v_add_f32_e32 v58, v58, v72
	v_add_f32_e32 v59, v59, v73
	s_nop 0
	v_add_f32_e32 v58, v58, v59
	s_nop 1
	v_add_f32_dpp v58, v58, v58 quad_perm:[1,0,3,2] row_mask:0xf bank_mask:0xf bound_ctrl:1
	s_nop 1
	v_add_f32_dpp v58, v58, v58 quad_perm:[2,3,0,1] row_mask:0xf bank_mask:0xf bound_ctrl:1
	s_nop 1
	v_add_f32_dpp v58, v58, v58 row_half_mirror row_mask:0xf bank_mask:0xf bound_ctrl:1
	s_nop 1
	v_add_f32_dpp v58, v58, v58 row_mirror row_mask:0xf bank_mask:0xf bound_ctrl:1
	s_nop 0
	v_readlane_b32 s8, v58, 16
	v_readlane_b32 s9, v58, 48
	v_readlane_b32 s6, v58, 0
	v_readlane_b32 s7, v58, 32
	v_mov_b32_e32 v58, s8
	v_mov_b32_e32 v59, s9
	v_add_f32_e32 v58, s6, v58
	v_add_f32_e32 v59, s7, v59
	s_nop 0
	v_add_f32_e32 v58, v58, v59
	v_fmamk_f32 v58, v58, 0x3a000000, v252
	v_mul_f32_e32 v59, 0x4f800000, v58
	v_cmp_gt_f32_e32 vcc, s55, v58
	s_nop 1
	v_cndmask_b32_e32 v58, v58, v59, vcc
	v_sqrt_f32_e32 v59, v58
	s_nop 0
	v_add_u32_e32 v72, -1, v59
	v_fma_f32 v73, -v72, v59, v58
	v_cmp_ge_f32_e64 s[8:9], 0, v73
	v_add_u32_e32 v73, 1, v59
	s_nop 0
	v_cndmask_b32_e64 v72, v59, v72, s[8:9]
	v_fma_f32 v59, -v73, v59, v58
	v_cmp_lt_f32_e64 s[8:9], 0, v59
	s_nop 1
	v_cndmask_b32_e64 v59, v72, v73, s[8:9]
	v_mul_f32_e32 v72, 0x37800000, v59
	v_cndmask_b32_e32 v59, v59, v72, vcc
	v_cmp_class_f32_e32 vcc, v58, v253
	s_nop 1
	v_cndmask_b32_e32 v58, v59, v58, vcc
	v_div_scale_f32 v59, s[6:7], v58, v58, 1.0
	v_rcp_f32_e32 v72, v59
	s_lshl_b64 s[6:7], s[10:11], 12
	v_lshl_add_u64 v[34:35], v[34:35], 0, s[6:7]
	v_lshl_add_u64 v[34:35], v[34:35], 0, v[0:1]
	v_fma_f32 v73, -v59, v72, 1.0
	v_fmac_f32_e32 v72, v73, v72
	v_div_scale_f32 v73, vcc, 1.0, v58, 1.0
	v_mul_f32_e32 v84, v73, v72
	v_fma_f32 v85, -v59, v84, v73
	v_fmac_f32_e32 v84, v85, v72
	v_fma_f32 v59, -v59, v84, v73
	v_div_fmas_f32 v59, v59, v72, v84
	v_div_fixup_f32 v58, v59, v58, 1.0
	v_mul_f32_e32 v52, v52, v58
	v_mul_f32_e32 v53, v53, v58
	v_mul_f32_e32 v46, v46, v58
	v_mul_f32_e32 v47, v47, v58
	v_lshlrev_b32_e32 v72, 16, v44
	v_and_b32_e32 v73, 0xffff0000, v44
	v_lshlrev_b32_e32 v44, 16, v45
	v_and_b32_e32 v45, 0xffff0000, v45
	v_mul_f32_e32 v2, v2, v46
	v_mul_f32_e32 v3, v3, v47
	v_mul_f32_e32 v4, v4, v52
	v_mul_f32_e32 v5, v5, v53
	v_mul_f32_e32 v2, v2, v72
	v_mul_f32_e32 v3, v3, v73
	v_mul_f32_e32 v4, v4, v44
	v_mul_f32_e32 v5, v5, v45
	v_cvt_pk_bf16_f32 v2, v2, v3
	v_cvt_pk_bf16_f32 v3, v4, v5
	global_store_dwordx2 v[34:35], v[2:3], off
	v_lshlrev_b32_e32 v2, 16, v40
	v_and_b32_e32 v3, 0xffff0000, v40
	v_lshlrev_b32_e32 v4, 16, v41
	v_and_b32_e32 v5, 0xffff0000, v41
	v_mul_f32_e32 v40, v48, v58
	v_mul_f32_e32 v41, v49, v58
	v_mul_f32_e32 v42, v42, v58
	v_mul_f32_e32 v43, v43, v58
	v_mul_f32_e32 v8, v8, v40
	v_mul_f32_e32 v9, v9, v41
	v_mul_f32_e32 v6, v6, v42
	v_mul_f32_e32 v7, v7, v43
	v_mul_f32_e32 v4, v8, v4
	v_mul_f32_e32 v5, v9, v5
	v_mul_f32_e32 v2, v6, v2
	v_mul_f32_e32 v3, v7, v3
	v_mul_f32_e32 v6, v60, v58
	v_mul_f32_e32 v7, v61, v58
	v_cvt_pk_bf16_f32 v2, v2, v3
	v_cvt_pk_bf16_f32 v3, v4, v5
	v_mul_f32_e32 v8, v54, v58
	v_mul_f32_e32 v9, v55, v58
	global_store_dwordx2 v[34:35], v[2:3], off offset:512
	v_lshlrev_b32_e32 v2, 16, v38
	v_and_b32_e32 v3, 0xffff0000, v38
	v_lshlrev_b32_e32 v4, 16, v39
	v_and_b32_e32 v5, 0xffff0000, v39
	v_mul_f32_e32 v8, v10, v8
	v_mul_f32_e32 v9, v11, v9
	v_mul_f32_e32 v6, v12, v6
	v_mul_f32_e32 v7, v13, v7
	v_mul_f32_e32 v2, v8, v2
	v_mul_f32_e32 v3, v9, v3
	v_mul_f32_e32 v4, v6, v4
	v_mul_f32_e32 v5, v7, v5
	v_cvt_pk_bf16_f32 v2, v2, v3
	v_cvt_pk_bf16_f32 v3, v4, v5
	v_mul_f32_e32 v6, v70, v58
	v_mul_f32_e32 v7, v71, v58
	v_mul_f32_e32 v8, v66, v58
	v_mul_f32_e32 v9, v67, v58
	global_store_dwordx2 v[34:35], v[2:3], off offset:1024
	v_lshlrev_b32_e32 v2, 16, v36
	v_and_b32_e32 v3, 0xffff0000, v36
	v_lshlrev_b32_e32 v4, 16, v37
	v_and_b32_e32 v5, 0xffff0000, v37
	v_mul_f32_e32 v8, v14, v8
	v_mul_f32_e32 v9, v15, v9
	v_mul_f32_e32 v6, v16, v6
	v_mul_f32_e32 v7, v17, v7
	v_mul_f32_e32 v2, v8, v2
	v_mul_f32_e32 v3, v9, v3
	v_mul_f32_e32 v4, v6, v4
	v_mul_f32_e32 v5, v7, v5
	v_cvt_pk_bf16_f32 v2, v2, v3
	v_cvt_pk_bf16_f32 v3, v4, v5
	v_mul_f32_e32 v6, v82, v58
	v_mul_f32_e32 v7, v83, v58
	v_mul_f32_e32 v8, v80, v58
	v_mul_f32_e32 v9, v81, v58
	global_store_dwordx2 v[34:35], v[2:3], off offset:1536
	s_waitcnt vmcnt(23)
	v_lshlrev_b32_e32 v2, 16, v90
	v_and_b32_e32 v3, 0xffff0000, v90
	v_lshlrev_b32_e32 v4, 16, v91
	v_and_b32_e32 v5, 0xffff0000, v91
	v_mul_f32_e32 v8, v18, v8
	v_mul_f32_e32 v9, v19, v9
	v_mul_f32_e32 v6, v20, v6
	v_mul_f32_e32 v7, v21, v7
	v_mul_f32_e32 v2, v8, v2
	v_mul_f32_e32 v3, v9, v3
	v_mul_f32_e32 v4, v6, v4
	v_mul_f32_e32 v5, v7, v5
	v_cvt_pk_bf16_f32 v2, v2, v3
	v_cvt_pk_bf16_f32 v3, v4, v5
	v_mul_f32_e32 v6, v62, v58
	v_mul_f32_e32 v7, v63, v58
	v_mul_f32_e32 v8, v64, v58
	v_mul_f32_e32 v9, v65, v58
	global_store_dwordx2 v[34:35], v[2:3], off offset:2048
	s_waitcnt vmcnt(23)
	v_lshlrev_b32_e32 v2, 16, v76
	v_and_b32_e32 v3, 0xffff0000, v76
	v_lshlrev_b32_e32 v4, 16, v77
	v_and_b32_e32 v5, 0xffff0000, v77
	v_mul_f32_e32 v8, v22, v8
	v_mul_f32_e32 v9, v23, v9
	v_mul_f32_e32 v6, v24, v6
	v_mul_f32_e32 v7, v25, v7
	v_mul_f32_e32 v2, v8, v2
	v_mul_f32_e32 v3, v9, v3
	v_mul_f32_e32 v4, v6, v4
	v_mul_f32_e32 v5, v7, v5
	v_cvt_pk_bf16_f32 v2, v2, v3
	v_cvt_pk_bf16_f32 v3, v4, v5
	v_mul_f32_e32 v6, v56, v58
	v_mul_f32_e32 v7, v57, v58
	v_mul_f32_e32 v8, v78, v58
	v_mul_f32_e32 v9, v79, v58
	global_store_dwordx2 v[34:35], v[2:3], off offset:2560
	s_waitcnt vmcnt(23)
	v_lshlrev_b32_e32 v2, 16, v74
	v_and_b32_e32 v3, 0xffff0000, v74
	v_lshlrev_b32_e32 v4, 16, v75
	v_and_b32_e32 v5, 0xffff0000, v75
	v_mul_f32_e32 v8, v26, v8
	v_mul_f32_e32 v9, v27, v9
	v_mul_f32_e32 v6, v28, v6
	v_mul_f32_e32 v7, v29, v7
	v_mul_f32_e32 v2, v8, v2
	v_mul_f32_e32 v3, v9, v3
	v_mul_f32_e32 v4, v6, v4
	v_mul_f32_e32 v5, v7, v5
	v_cvt_pk_bf16_f32 v2, v2, v3
	v_cvt_pk_bf16_f32 v3, v4, v5
	v_mul_f32_e32 v6, v50, v58
	v_mul_f32_e32 v7, v51, v58
	v_mul_f32_e32 v8, v88, v58
	v_mul_f32_e32 v9, v89, v58
	global_store_dwordx2 v[34:35], v[2:3], off offset:3072
	s_waitcnt vmcnt(23)
	v_lshlrev_b32_e32 v2, 16, v68
	v_and_b32_e32 v3, 0xffff0000, v68
	v_lshlrev_b32_e32 v4, 16, v69
	v_and_b32_e32 v5, 0xffff0000, v69
	v_mul_f32_e32 v8, v30, v8
	v_mul_f32_e32 v9, v31, v9
	v_mul_f32_e32 v6, v32, v6
	v_mul_f32_e32 v7, v33, v7
	v_mul_f32_e32 v2, v8, v2
	v_mul_f32_e32 v3, v9, v3
	v_mul_f32_e32 v4, v6, v4
	v_mul_f32_e32 v5, v7, v5
	v_cvt_pk_bf16_f32 v2, v2, v3
	v_cvt_pk_bf16_f32 v3, v4, v5
	global_store_dwordx2 v[34:35], v[2:3], off offset:3584

; __device__ __forceinline__ u32x4 pack8(f32x4 v0, f32x4 v1) { u32x4 w; w.x = cvt_pk_bf16(v0[0], v0[1]); w.y = cvt_pk_bf16(v0[2], v0[3]); w.z = cvt_pk_bf16(v1[0], v1[1]); w.w = cvt_pk_bf16(v1[2], v1[3]); return w; }
; __device__ __forceinline__ float fast_sigmoid(float x) { return __builtin_amdgcn_rcpf(1.0f + __expf(-x)); }
; __device__ __forceinline__ f32x4 sigm4(f32x4 v) { const f32x4 t = v * -1.4426950408889634f; f32x4 e = {__builtin_amdgcn_exp2f(t[0]), __builtin_amdgcn_exp2f(t[1]), __builtin_amdgcn_exp2f(t[2]), __builtin_amdgcn_exp2f(t[3])};
;     e = e + 1.0f; return (f32x4){__builtin_amdgcn_rcpf(e[0]), __builtin_amdgcn_rcpf(e[1]), __builtin_amdgcn_rcpf(e[2]), __builtin_amdgcn_rcpf(e[3])}; }
; __device__ __forceinline__ f32x4 silu4(f32x4 v) { return v * sigm4(v); }
;     __device__ __forceinline__ void store_rows(const f32x4& a0, const f32x4& a1, const f32x4& b0, const f32x4& b1, int type, bf16_t* base, size_t off) const {
;         f32x4 x0 = a0, x1 = a1, y0 = b0, y1 = b1;
;         if (type == 1) { x0 = x0 * 0.0625f; x1 = x1 * 0.0625f; y0 = y0 * 0.0625f; y1 = y1 * 0.0625f; }
;         if (type == 3) { x0 = silu4(x0); x1 = silu4(x1); y0 = silu4(y0); y1 = silu4(y1); }
;         st16(base, off, pack8(x0, x1));
;         st16(base, off + HALF, pack8(y0, y1));
;     }
;     __device__ __forceinline__ void operator()(const f32x4 (&acc)[2][2][4][2], const Unit& u, int wr, int wc, int fr_in, int fq_in) const {
;         int fr = fr_in, fq = fq_in; asm volatile("" : "+v"(fr), "+v"(fq));
;         const int type = u.pn >> 3, head = u.pn & 7;
;         bf16_t* base = act + (size_t)type * tstride; const size_t coff = head * 256 + wc * 32 + 8 * fq;
;         const int row0 = u.pm * BM + wr * 64 + fr;
;         const bool rope = (type < 2) && (u.pm < n_lat_panels);
;         const int fidx = (wc & 1) * 32 + 8 * fq;
;         if (!rope) {
; #pragma unroll
;             for (int ai = 0; ai < 2; ++ai)
; #pragma unroll
;                 for (int m = 0; m < 4; ++m) store_rows(acc[ai][0][m][0], acc[ai][0][m][1], acc[ai][1][m][0], acc[ai][1][m][1], type, base, (size_t)(row0 + ai * HALF + m * 16) * 2048 + coff);
.LBB0_652:
	s_ashr_i32 s23, s34, 3
	s_mul_i32 s7, s23, 0x4400000
	s_mul_hi_i32 s6, s23, 0x4400000
	s_add_u32 s30, s70, s7
	s_addc_u32 s31, s71, s6
	s_lshl_b32 s6, s34, 8
	s_and_b32 s6, s6, 0x700
	s_lshl_b32 s21, s8, 8
	v_mov_b32_e32 v0, v175
	v_mov_b32_e32 v152, v174
	s_or_b32 s6, s6, s78
	s_add_i32 s21, s21, s69
	s_cmp_lt_i32 s23, 2
	v_lshlrev_b32_e32 v153, 3, v0
	v_add_u32_e32 v148, s6, v153
	s_cselect_b64 s[6:7], -1, 0
	s_cmp_lt_i32 s8, 64
	s_cselect_b64 s[8:9], -1, 0
	s_and_b64 s[8:9], s[6:7], s[8:9]
	v_ashrrev_i32_e32 v149, 31, v148
	v_add_u32_e32 v2, s21, v152
	s_mov_b64 s[6:7], -1
	s_and_b64 vcc, exec, s[8:9]
	s_movk_i32 s94, 0x7ff
	s_cbranch_vccnz .LBB0_686
	s_cmp_eq_u32 s23, 1
	v_mov_b64_e32 v[138:139], v[122:123]
	v_mov_b64_e32 v[146:147], v[118:119]
	v_mov_b64_e32 v[134:135], v[130:131]
	v_mov_b64_e32 v[142:143], v[126:127]
	s_cselect_b64 s[8:9], -1, 0
	s_cmp_lg_u32 s23, 1
	v_mov_b64_e32 v[136:137], v[120:121]
	v_mov_b64_e32 v[144:145], v[116:117]
	v_mov_b64_e32 v[132:133], v[128:129]
	v_mov_b64_e32 v[140:141], v[124:125]
	s_cbranch_scc1 .LBB0_655
	v_mul_f32_e32 v138, s54, v122
	v_mul_f32_e32 v139, s54, v123
	v_mul_f32_e32 v136, s54, v120
	v_mul_f32_e32 v137, s54, v121
	v_mul_f32_e32 v146, s54, v118
	v_mul_f32_e32 v147, s54, v119
	v_mul_f32_e32 v144, s54, v116
	v_mul_f32_e32 v145, s54, v117
	v_mul_f32_e32 v134, s54, v130
	v_mul_f32_e32 v135, s54, v131
	v_mul_f32_e32 v132, s54, v128
	v_mul_f32_e32 v133, s54, v129
	v_mul_f32_e32 v142, s54, v126
	v_mul_f32_e32 v143, s54, v127
	v_mul_f32_e32 v140, s54, v124
	v_mul_f32_e32 v141, s54, v125
.LBB0_655:
	s_cmp_eq_u32 s23, 3
	s_cselect_b64 s[34:35], -1, 0
	s_cmp_lg_u32 s23, 3
	s_cbranch_scc1 .LBB0_657
	v_mul_f32_e32 v150, s96, v138
	v_mul_f32_e32 v151, s96, v139
	v_mul_f32_e32 v154, s96, v136
	v_mul_f32_e32 v155, s96, v137
	v_exp_f32_e32 v150, v150
	v_exp_f32_e32 v154, v154
	v_exp_f32_e32 v155, v155
	v_exp_f32_e32 v151, v151
	v_add_f32_e32 v154, 1.0, v154
	v_add_f32_e32 v155, 1.0, v155
	v_add_f32_e32 v150, 1.0, v150
	v_add_f32_e32 v151, 1.0, v151
	v_rcp_f32_e32 v154, v154
	v_rcp_f32_e32 v155, v155
	v_rcp_f32_e32 v150, v150
	v_rcp_f32_e32 v151, v151
	v_mul_f32_e32 v136, v136, v154
	v_mul_f32_e32 v137, v137, v155
	v_mul_f32_e32 v154, s96, v144
	v_mul_f32_e32 v155, s96, v145
	v_mul_f32_e32 v138, v138, v150
	v_mul_f32_e32 v139, v139, v151
	v_mul_f32_e32 v150, s96, v146
	v_mul_f32_e32 v151, s96, v147
	v_exp_f32_e32 v154, v154
	v_exp_f32_e32 v155, v155
	v_exp_f32_e32 v150, v150
	v_exp_f32_e32 v151, v151
	v_add_f32_e32 v154, 1.0, v154
	v_add_f32_e32 v155, 1.0, v155
	s_nop 0
	v_rcp_f32_e32 v154, v154
	v_add_f32_e32 v150, 1.0, v150
	v_add_f32_e32 v151, 1.0, v151
	v_rcp_f32_e32 v155, v155
	v_rcp_f32_e32 v150, v150
	v_rcp_f32_e32 v151, v151
	v_mul_f32_e32 v144, v144, v154
	v_mul_f32_e32 v145, v145, v155
	v_mul_f32_e32 v154, s96, v132
	v_mul_f32_e32 v155, s96, v133
	v_mul_f32_e32 v146, v146, v150
	v_mul_f32_e32 v147, v147, v151
	v_mul_f32_e32 v150, s96, v134
	v_mul_f32_e32 v151, s96, v135
	v_exp_f32_e32 v154, v154
	v_exp_f32_e32 v155, v155
	v_exp_f32_e32 v150, v150
	v_exp_f32_e32 v151, v151
	v_add_f32_e32 v154, 1.0, v154
	v_add_f32_e32 v155, 1.0, v155
	s_nop 0
	v_rcp_f32_e32 v154, v154
	v_add_f32_e32 v150, 1.0, v150
	v_add_f32_e32 v151, 1.0, v151
	v_rcp_f32_e32 v155, v155
	v_rcp_f32_e32 v150, v150
	v_rcp_f32_e32 v151, v151
	v_mul_f32_e32 v132, v132, v154
	v_mul_f32_e32 v133, v133, v155
	v_mul_f32_e32 v154, s96, v140
	v_mul_f32_e32 v155, s96, v141
	v_mul_f32_e32 v134, v134, v150
	v_mul_f32_e32 v135, v135, v151
	v_mul_f32_e32 v150, s96, v142
	v_mul_f32_e32 v151, s96, v143
	v_exp_f32_e32 v154, v154
	v_exp_f32_e32 v155, v155
	v_exp_f32_e32 v150, v150
	v_exp_f32_e32 v151, v151
	v_add_f32_e32 v154, 1.0, v154
	v_add_f32_e32 v155, 1.0, v155
	s_nop 0
	v_rcp_f32_e32 v154, v154
	v_add_f32_e32 v150, 1.0, v150
	v_add_f32_e32 v151, 1.0, v151
	v_rcp_f32_e32 v155, v155
	v_rcp_f32_e32 v150, v150
	v_rcp_f32_e32 v151, v151
	v_mul_f32_e32 v140, v140, v154
	v_mul_f32_e32 v141, v141, v155
	v_mul_f32_e32 v142, v142, v150
	v_mul_f32_e32 v143, v143, v151
.LBB0_657:
	v_lshlrev_b64 v[150:151], 1, v[148:149]
	v_lshl_add_u32 v0, v2, 12, v150
	v_cvt_pk_bf16_f32 v136, v136, v137
	v_cvt_pk_bf16_f32 v137, v138, v139
	v_cvt_pk_bf16_f32 v138, v144, v145
	v_lshl_add_u64 v[144:145], s[30:31], 0, v[0:1]
	v_cvt_pk_bf16_f32 v139, v146, v147
	global_store_dwordx4 v[144:145], v[136:139], off
	v_cvt_pk_bf16_f32 v132, v132, v133
	v_cvt_pk_bf16_f32 v133, v134, v135
	v_cvt_pk_bf16_f32 v134, v140, v141
	v_cvt_pk_bf16_f32 v135, v142, v143
	v_add_u32_e32 v3, 0x100, v0
	global_store_dwordx4 v3, v[132:135], s[30:31]
	v_cndmask_b32_e64 v3, 0, 1, s[8:9]
	v_mov_b64_e32 v[138:139], v[106:107]
	v_mov_b64_e32 v[146:147], v[102:103]
	v_mov_b64_e32 v[134:135], v[114:115]
	v_mov_b64_e32 v[142:143], v[110:111]
	v_cmp_ne_u32_e64 s[6:7], 1, v3
	s_andn2_b64 vcc, exec, s[8:9]
	v_mov_b64_e32 v[136:137], v[104:105]
	v_mov_b64_e32 v[144:145], v[100:101]
	v_mov_b64_e32 v[132:133], v[112:113]
	v_mov_b64_e32 v[140:141], v[108:109]
	s_cbranch_vccnz .LBB0_659
	v_mul_f32_e32 v138, s54, v106
	v_mul_f32_e32 v139, s54, v107
	v_mul_f32_e32 v136, s54, v104
	v_mul_f32_e32 v137, s54, v105
	v_mul_f32_e32 v146, s54, v102
	v_mul_f32_e32 v147, s54, v103
	v_mul_f32_e32 v144, s54, v100
	v_mul_f32_e32 v145, s54, v101
	v_mul_f32_e32 v134, s54, v114
	v_mul_f32_e32 v135, s54, v115
	v_mul_f32_e32 v132, s54, v112
	v_mul_f32_e32 v133, s54, v113
	v_mul_f32_e32 v142, s54, v110
	v_mul_f32_e32 v143, s54, v111
	v_mul_f32_e32 v140, s54, v108
	v_mul_f32_e32 v141, s54, v109
; __device__ __forceinline__ u32x4 pack8(f32x4 v0, f32x4 v1) { u32x4 w; w.x = cvt_pk_bf16(v0[0], v0[1]); w.y = cvt_pk_bf16(v0[2], v0[3]); w.z = cvt_pk_bf16(v1[0], v1[1]); w.w = cvt_pk_bf16(v1[2], v1[3]); return w; }
; __device__ __forceinline__ f32x4 sigm4(f32x4 v) { const f32x4 t = v * -1.4426950408889634f; f32x4 e = {__builtin_amdgcn_exp2f(t[0]), __builtin_amdgcn_exp2f(t[1]), __builtin_amdgcn_exp2f(t[2]), __builtin_amdgcn_exp2f(t[3])};
;     e = e + 1.0f; return (f32x4){__builtin_amdgcn_rcpf(e[0]), __builtin_amdgcn_rcpf(e[1]), __builtin_amdgcn_rcpf(e[2]), __builtin_amdgcn_rcpf(e[3])}; }
; __device__ __forceinline__ f32x4 silu4(f32x4 v) { return v * sigm4(v); }
;     __device__ __forceinline__ void store_rows(const f32x4& a0, const f32x4& a1, const f32x4& b0, const f32x4& b1, int type, bf16_t* base, size_t off) const {
;         f32x4 x0 = a0, x1 = a1, y0 = b0, y1 = b1;
;         if (type == 1) { x0 = x0 * 0.0625f; x1 = x1 * 0.0625f; y0 = y0 * 0.0625f; y1 = y1 * 0.0625f; }
;         if (type == 3) { x0 = silu4(x0); x1 = silu4(x1); y0 = silu4(y0); y1 = silu4(y1); }
;         st16(base, off, pack8(x0, x1));
;         st16(base, off + HALF, pack8(y0, y1));
.LBB0_659:
	v_cndmask_b32_e64 v3, 0, 1, s[34:35]
	v_cmp_ne_u32_e64 s[8:9], 1, v3
	s_andn2_b64 vcc, exec, s[34:35]
	s_cbranch_vccnz .LBB0_661
	v_mul_f32_e32 v154, s96, v138
	v_mul_f32_e32 v155, s96, v139
	v_mul_f32_e32 v156, s96, v136
	v_mul_f32_e32 v157, s96, v137
	v_exp_f32_e32 v154, v154
	v_exp_f32_e32 v156, v156
	v_exp_f32_e32 v157, v157
	v_exp_f32_e32 v155, v155
	v_add_f32_e32 v156, 1.0, v156
	v_add_f32_e32 v157, 1.0, v157
	v_add_f32_e32 v154, 1.0, v154
	v_add_f32_e32 v155, 1.0, v155
	v_rcp_f32_e32 v156, v156
	v_rcp_f32_e32 v157, v157
	v_rcp_f32_e32 v154, v154
	v_rcp_f32_e32 v155, v155
	v_mul_f32_e32 v136, v136, v156
	v_mul_f32_e32 v137, v137, v157
	v_mul_f32_e32 v156, s96, v144
	v_mul_f32_e32 v157, s96, v145
	v_mul_f32_e32 v138, v138, v154
	v_mul_f32_e32 v139, v139, v155
	v_mul_f32_e32 v154, s96, v146
	v_mul_f32_e32 v155, s96, v147
	v_exp_f32_e32 v156, v156
	v_exp_f32_e32 v157, v157
	v_exp_f32_e32 v154, v154
	v_exp_f32_e32 v155, v155
	v_add_f32_e32 v156, 1.0, v156
	v_add_f32_e32 v157, 1.0, v157
	s_nop 0
	v_rcp_f32_e32 v156, v156
	v_add_f32_e32 v154, 1.0, v154
	v_add_f32_e32 v155, 1.0, v155
	v_rcp_f32_e32 v157, v157
	v_rcp_f32_e32 v154, v154
	v_rcp_f32_e32 v155, v155
	v_mul_f32_e32 v144, v144, v156
	v_mul_f32_e32 v145, v145, v157
	v_mul_f32_e32 v156, s96, v132
	v_mul_f32_e32 v157, s96, v133
	v_mul_f32_e32 v146, v146, v154
	v_mul_f32_e32 v147, v147, v155
	v_mul_f32_e32 v154, s96, v134
	v_mul_f32_e32 v155, s96, v135
	v_exp_f32_e32 v156, v156
	v_exp_f32_e32 v157, v157
	v_exp_f32_e32 v154, v154
	v_exp_f32_e32 v155, v155
	v_add_f32_e32 v156, 1.0, v156
	v_add_f32_e32 v157, 1.0, v157
	s_nop 0
	v_rcp_f32_e32 v156, v156
	v_add_f32_e32 v154, 1.0, v154
	v_add_f32_e32 v155, 1.0, v155
	v_rcp_f32_e32 v157, v157
	v_rcp_f32_e32 v154, v154
	v_rcp_f32_e32 v155, v155
	v_mul_f32_e32 v132, v132, v156
	v_mul_f32_e32 v133, v133, v157
	v_mul_f32_e32 v156, s96, v140
	v_mul_f32_e32 v157, s96, v141
	v_mul_f32_e32 v134, v134, v154
	v_mul_f32_e32 v135, v135, v155
	v_mul_f32_e32 v154, s96, v142
	v_mul_f32_e32 v155, s96, v143
	v_exp_f32_e32 v156, v156
	v_exp_f32_e32 v157, v157
	v_exp_f32_e32 v154, v154
	v_exp_f32_e32 v155, v155
	v_add_f32_e32 v156, 1.0, v156
	v_add_f32_e32 v157, 1.0, v157
	s_nop 0
	v_rcp_f32_e32 v156, v156
	v_add_f32_e32 v154, 1.0, v154
	v_add_f32_e32 v155, 1.0, v155
	v_rcp_f32_e32 v157, v157
	v_rcp_f32_e32 v154, v154
	v_rcp_f32_e32 v155, v155
	v_mul_f32_e32 v140, v140, v156
	v_mul_f32_e32 v141, v141, v157
	v_mul_f32_e32 v142, v142, v154
	v_mul_f32_e32 v143, v143, v155
.LBB0_661:
	v_add_u32_e32 v3, 0x10000, v0
	v_cvt_pk_bf16_f32 v136, v136, v137
	v_cvt_pk_bf16_f32 v137, v138, v139
	v_cvt_pk_bf16_f32 v138, v144, v145
	v_and_b32_e32 v144, -2, v3
	v_mov_b32_e32 v145, v1
	v_lshl_add_u64 v[144:145], s[30:31], 0, v[144:145]
	v_add_u32_e32 v3, 0x10100, v0
	v_cvt_pk_bf16_f32 v139, v146, v147
	global_store_dwordx4 v[144:145], v[136:139], off
	v_cvt_pk_bf16_f32 v132, v132, v133
	v_cvt_pk_bf16_f32 v133, v134, v135
	v_cvt_pk_bf16_f32 v134, v140, v141
	v_cvt_pk_bf16_f32 v135, v142, v143
	v_and_b32_e32 v3, -2, v3
	global_store_dwordx4 v3, v[132:135], s[30:31]
	v_mov_b64_e32 v[138:139], v[90:91]
	v_mov_b64_e32 v[146:147], v[86:87]
	v_mov_b64_e32 v[134:135], v[98:99]
	v_mov_b64_e32 v[142:143], v[94:95]
	s_and_b64 vcc, exec, s[6:7]
	v_mov_b64_e32 v[136:137], v[88:89]
	v_mov_b64_e32 v[144:145], v[84:85]
	v_mov_b64_e32 v[132:133], v[96:97]
	v_mov_b64_e32 v[140:141], v[92:93]
	s_cbranch_vccnz .LBB0_663
	v_mul_f32_e32 v138, s54, v90
	v_mul_f32_e32 v139, s54, v91
	v_mul_f32_e32 v136, s54, v88
	v_mul_f32_e32 v137, s54, v89
	v_mul_f32_e32 v146, s54, v86
	v_mul_f32_e32 v147, s54, v87
	v_mul_f32_e32 v144, s54, v84
	v_mul_f32_e32 v145, s54, v85
	v_mul_f32_e32 v134, s54, v98
	v_mul_f32_e32 v135, s54, v99
	v_mul_f32_e32 v132, s54, v96
	v_mul_f32_e32 v133, s54, v97
	v_mul_f32_e32 v142, s54, v94
	v_mul_f32_e32 v143, s54, v95
	v_mul_f32_e32 v140, s54, v92
	v_mul_f32_e32 v141, s54, v93
; __device__ __forceinline__ u32x4 pack8(f32x4 v0, f32x4 v1) { u32x4 w; w.x = cvt_pk_bf16(v0[0], v0[1]); w.y = cvt_pk_bf16(v0[2], v0[3]); w.z = cvt_pk_bf16(v1[0], v1[1]); w.w = cvt_pk_bf16(v1[2], v1[3]); return w; }
; __device__ __forceinline__ f32x4 sigm4(f32x4 v) { const f32x4 t = v * -1.4426950408889634f; f32x4 e = {__builtin_amdgcn_exp2f(t[0]), __builtin_amdgcn_exp2f(t[1]), __builtin_amdgcn_exp2f(t[2]), __builtin_amdgcn_exp2f(t[3])};
;     e = e + 1.0f; return (f32x4){__builtin_amdgcn_rcpf(e[0]), __builtin_amdgcn_rcpf(e[1]), __builtin_amdgcn_rcpf(e[2]), __builtin_amdgcn_rcpf(e[3])}; }
; __device__ __forceinline__ f32x4 silu4(f32x4 v) { return v * sigm4(v); }
;     __device__ __forceinline__ void store_rows(const f32x4& a0, const f32x4& a1, const f32x4& b0, const f32x4& b1, int type, bf16_t* base, size_t off) const {
;         f32x4 x0 = a0, x1 = a1, y0 = b0, y1 = b1;
;         if (type == 1) { x0 = x0 * 0.0625f; x1 = x1 * 0.0625f; y0 = y0 * 0.0625f; y1 = y1 * 0.0625f; }
;         if (type == 3) { x0 = silu4(x0); x1 = silu4(x1); y0 = silu4(y0); y1 = silu4(y1); }
;         st16(base, off, pack8(x0, x1));
;         st16(base, off + HALF, pack8(y0, y1));
.LBB0_663:
	s_and_b64 vcc, exec, s[8:9]
	s_cbranch_vccnz .LBB0_665
	v_mul_f32_e32 v154, s96, v138
	v_mul_f32_e32 v155, s96, v139
	v_mul_f32_e32 v156, s96, v136
	v_mul_f32_e32 v157, s96, v137
	v_exp_f32_e32 v154, v154
	v_exp_f32_e32 v156, v156
	v_exp_f32_e32 v157, v157
	v_exp_f32_e32 v155, v155
	v_add_f32_e32 v156, 1.0, v156
	v_add_f32_e32 v157, 1.0, v157
	v_add_f32_e32 v154, 1.0, v154
	v_add_f32_e32 v155, 1.0, v155
	v_rcp_f32_e32 v156, v156
	v_rcp_f32_e32 v157, v157
	v_rcp_f32_e32 v154, v154
	v_rcp_f32_e32 v155, v155
	v_mul_f32_e32 v136, v136, v156
	v_mul_f32_e32 v137, v137, v157
	v_mul_f32_e32 v156, s96, v144
	v_mul_f32_e32 v157, s96, v145
	v_mul_f32_e32 v138, v138, v154
	v_mul_f32_e32 v139, v139, v155
	v_mul_f32_e32 v154, s96, v146
	v_mul_f32_e32 v155, s96, v147
	v_exp_f32_e32 v156, v156
	v_exp_f32_e32 v157, v157
	v_exp_f32_e32 v154, v154
	v_exp_f32_e32 v155, v155
	v_add_f32_e32 v156, 1.0, v156
	v_add_f32_e32 v157, 1.0, v157
	s_nop 0
	v_rcp_f32_e32 v156, v156
	v_add_f32_e32 v154, 1.0, v154
	v_add_f32_e32 v155, 1.0, v155
	v_rcp_f32_e32 v157, v157
	v_rcp_f32_e32 v154, v154
	v_rcp_f32_e32 v155, v155
	v_mul_f32_e32 v144, v144, v156
	v_mul_f32_e32 v145, v145, v157
	v_mul_f32_e32 v156, s96, v132
	v_mul_f32_e32 v157, s96, v133
	v_mul_f32_e32 v146, v146, v154
	v_mul_f32_e32 v147, v147, v155
	v_mul_f32_e32 v154, s96, v134
	v_mul_f32_e32 v155, s96, v135
	v_exp_f32_e32 v156, v156
	v_exp_f32_e32 v157, v157
	v_exp_f32_e32 v154, v154
	v_exp_f32_e32 v155, v155
	v_add_f32_e32 v156, 1.0, v156
	v_add_f32_e32 v157, 1.0, v157
	s_nop 0
	v_rcp_f32_e32 v156, v156
	v_add_f32_e32 v154, 1.0, v154
	v_add_f32_e32 v155, 1.0, v155
	v_rcp_f32_e32 v157, v157
	v_rcp_f32_e32 v154, v154
	v_rcp_f32_e32 v155, v155
	v_mul_f32_e32 v132, v132, v156
	v_mul_f32_e32 v133, v133, v157
	v_mul_f32_e32 v156, s96, v140
	v_mul_f32_e32 v157, s96, v141
	v_mul_f32_e32 v134, v134, v154
	v_mul_f32_e32 v135, v135, v155
	v_mul_f32_e32 v154, s96, v142
	v_mul_f32_e32 v155, s96, v143
	v_exp_f32_e32 v156, v156
	v_exp_f32_e32 v157, v157
	v_exp_f32_e32 v154, v154
	v_exp_f32_e32 v155, v155
	v_add_f32_e32 v156, 1.0, v156
	v_add_f32_e32 v157, 1.0, v157
	s_nop 0
	v_rcp_f32_e32 v156, v156
	v_add_f32_e32 v154, 1.0, v154
	v_add_f32_e32 v155, 1.0, v155
	v_rcp_f32_e32 v157, v157
	v_rcp_f32_e32 v154, v154
	v_rcp_f32_e32 v155, v155
	v_mul_f32_e32 v140, v140, v156
	v_mul_f32_e32 v141, v141, v157
	v_mul_f32_e32 v142, v142, v154
	v_mul_f32_e32 v143, v143, v155
.LBB0_665:
	v_add_u32_e32 v3, 0x20000, v0
	v_cvt_pk_bf16_f32 v136, v136, v137
	v_cvt_pk_bf16_f32 v137, v138, v139
	v_cvt_pk_bf16_f32 v138, v144, v145
	v_and_b32_e32 v144, -2, v3
	v_mov_b32_e32 v145, v1
	v_lshl_add_u64 v[144:145], s[30:31], 0, v[144:145]
	v_add_u32_e32 v3, 0x20100, v0
	v_cvt_pk_bf16_f32 v139, v146, v147
	global_store_dwordx4 v[144:145], v[136:139], off
	v_cvt_pk_bf16_f32 v132, v132, v133
	v_cvt_pk_bf16_f32 v133, v134, v135
	v_cvt_pk_bf16_f32 v134, v140, v141
	v_cvt_pk_bf16_f32 v135, v142, v143
	v_and_b32_e32 v3, -2, v3
	global_store_dwordx4 v3, v[132:135], s[30:31]
	v_mov_b64_e32 v[138:139], v[74:75]
	v_mov_b64_e32 v[146:147], v[70:71]
	v_mov_b64_e32 v[134:135], v[82:83]
	v_mov_b64_e32 v[142:143], v[78:79]
	s_and_b64 vcc, exec, s[6:7]
	v_mov_b64_e32 v[136:137], v[72:73]
	v_mov_b64_e32 v[144:145], v[68:69]
	v_mov_b64_e32 v[132:133], v[80:81]
	v_mov_b64_e32 v[140:141], v[76:77]
	s_cbranch_vccnz .LBB0_667
	v_mul_f32_e32 v138, s54, v74
	v_mul_f32_e32 v139, s54, v75
	v_mul_f32_e32 v136, s54, v72
	v_mul_f32_e32 v137, s54, v73
	v_mul_f32_e32 v146, s54, v70
	v_mul_f32_e32 v147, s54, v71
	v_mul_f32_e32 v144, s54, v68
	v_mul_f32_e32 v145, s54, v69
	v_mul_f32_e32 v134, s54, v82
	v_mul_f32_e32 v135, s54, v83
	v_mul_f32_e32 v132, s54, v80
	v_mul_f32_e32 v133, s54, v81
	v_mul_f32_e32 v142, s54, v78
	v_mul_f32_e32 v143, s54, v79
	v_mul_f32_e32 v140, s54, v76
	v_mul_f32_e32 v141, s54, v77

; __device__ __forceinline__ f32x4 silu4(f32x4 v) { return v * sigm4(v); }
; __device__ __forceinline__ u32x4 pack8(f32x4 v0, f32x4 v1) { u32x4 w; w.x = cvt_pk_bf16(v0[0], v0[1]); w.y = cvt_pk_bf16(v0[2], v0[3]); w.z = cvt_pk_bf16(v1[0], v1[1]); w.w = cvt_pk_bf16(v1[2], v1[3]); return w; }
;     __device__ __forceinline__ void store_rows(const f32x4& a0, const f32x4& a1, const f32x4& b0, const f32x4& b1, int type, bf16_t* base, size_t off) const {
;         f32x4 x0 = a0, x1 = a1, y0 = b0, y1 = b1;
;         if (type == 1) { x0 = x0 * 0.0625f; x1 = x1 * 0.0625f; y0 = y0 * 0.0625f; y1 = y1 * 0.0625f; }
;         if (type == 3) { x0 = silu4(x0); x1 = silu4(x1); y0 = silu4(y0); y1 = silu4(y1); }
;         st16(base, off, pack8(x0, x1));
;         st16(base, off + HALF, pack8(y0, y1));
.LBB0_669:
	v_add_u32_e32 v3, 0x30000, v0
	v_cvt_pk_bf16_f32 v136, v136, v137
	v_cvt_pk_bf16_f32 v137, v138, v139
	v_cvt_pk_bf16_f32 v138, v144, v145
	v_and_b32_e32 v144, -2, v3
	v_mov_b32_e32 v145, v1
	v_lshl_add_u64 v[144:145], s[30:31], 0, v[144:145]
	v_add_u32_e32 v3, 0x30100, v0
	v_cvt_pk_bf16_f32 v139, v146, v147
	global_store_dwordx4 v[144:145], v[136:139], off
	v_cvt_pk_bf16_f32 v132, v132, v133
	v_cvt_pk_bf16_f32 v133, v134, v135
	v_cvt_pk_bf16_f32 v134, v140, v141
	v_cvt_pk_bf16_f32 v135, v142, v143
	v_and_b32_e32 v3, -2, v3
	global_store_dwordx4 v3, v[132:135], s[30:31]
	v_mov_b64_e32 v[138:139], v[58:59]
	v_mov_b64_e32 v[146:147], v[54:55]
	v_mov_b64_e32 v[134:135], v[66:67]
	v_mov_b64_e32 v[142:143], v[62:63]
	s_and_b64 vcc, exec, s[6:7]
	v_mov_b64_e32 v[136:137], v[56:57]
	v_mov_b64_e32 v[144:145], v[52:53]
	v_mov_b64_e32 v[132:133], v[64:65]
	v_mov_b64_e32 v[140:141], v[60:61]
	s_cbranch_vccnz .LBB0_671
	v_mul_f32_e32 v138, s54, v58
	v_mul_f32_e32 v139, s54, v59
	v_mul_f32_e32 v136, s54, v56
	v_mul_f32_e32 v137, s54, v57
	v_mul_f32_e32 v146, s54, v54
	v_mul_f32_e32 v147, s54, v55
	v_mul_f32_e32 v144, s54, v52
	v_mul_f32_e32 v145, s54, v53
	v_mul_f32_e32 v134, s54, v66
	v_mul_f32_e32 v135, s54, v67
	v_mul_f32_e32 v132, s54, v64
	v_mul_f32_e32 v133, s54, v65
	v_mul_f32_e32 v142, s54, v62
	v_mul_f32_e32 v143, s54, v63
	v_mul_f32_e32 v140, s54, v60
	v_mul_f32_e32 v141, s54, v61

; __device__ __forceinline__ f32x4 silu4(f32x4 v) { return v * sigm4(v); }
; __device__ __forceinline__ u32x4 pack8(f32x4 v0, f32x4 v1) { u32x4 w; w.x = cvt_pk_bf16(v0[0], v0[1]); w.y = cvt_pk_bf16(v0[2], v0[3]); w.z = cvt_pk_bf16(v1[0], v1[1]); w.w = cvt_pk_bf16(v1[2], v1[3]); return w; }
;     __device__ __forceinline__ void store_rows(const f32x4& a0, const f32x4& a1, const f32x4& b0, const f32x4& b1, int type, bf16_t* base, size_t off) const {
;         f32x4 x0 = a0, x1 = a1, y0 = b0, y1 = b1;
;         if (type == 1) { x0 = x0 * 0.0625f; x1 = x1 * 0.0625f; y0 = y0 * 0.0625f; y1 = y1 * 0.0625f; }
;         if (type == 3) { x0 = silu4(x0); x1 = silu4(x1); y0 = silu4(y0); y1 = silu4(y1); }
;         st16(base, off, pack8(x0, x1));
;         st16(base, off + HALF, pack8(y0, y1));
.LBB0_673:
	v_add_u32_e32 v3, 0x80000, v0
	v_cvt_pk_bf16_f32 v136, v136, v137
	v_cvt_pk_bf16_f32 v137, v138, v139
	v_cvt_pk_bf16_f32 v138, v144, v145
	v_and_b32_e32 v144, -2, v3
	v_mov_b32_e32 v145, v1
	v_lshl_add_u64 v[144:145], s[30:31], 0, v[144:145]
	v_add_u32_e32 v3, 0x80100, v0
	v_cvt_pk_bf16_f32 v139, v146, v147
	global_store_dwordx4 v[144:145], v[136:139], off
	v_cvt_pk_bf16_f32 v132, v132, v133
	v_cvt_pk_bf16_f32 v133, v134, v135
	v_cvt_pk_bf16_f32 v134, v140, v141
	v_cvt_pk_bf16_f32 v135, v142, v143
	v_and_b32_e32 v3, -2, v3
	global_store_dwordx4 v3, v[132:135], s[30:31]
	v_mov_b64_e32 v[138:139], v[42:43]
	v_mov_b64_e32 v[146:147], v[38:39]
	v_mov_b64_e32 v[134:135], v[50:51]
	v_mov_b64_e32 v[142:143], v[46:47]
	s_and_b64 vcc, exec, s[6:7]
	v_mov_b64_e32 v[136:137], v[40:41]
	v_mov_b64_e32 v[144:145], v[36:37]
	v_mov_b64_e32 v[132:133], v[48:49]
	v_mov_b64_e32 v[140:141], v[44:45]
	s_cbranch_vccnz .LBB0_675
	v_mul_f32_e32 v138, s54, v42
	v_mul_f32_e32 v139, s54, v43
	v_mul_f32_e32 v136, s54, v40
	v_mul_f32_e32 v137, s54, v41
	v_mul_f32_e32 v146, s54, v38
	v_mul_f32_e32 v147, s54, v39
	v_mul_f32_e32 v144, s54, v36
	v_mul_f32_e32 v145, s54, v37
	v_mul_f32_e32 v134, s54, v50
	v_mul_f32_e32 v135, s54, v51
	v_mul_f32_e32 v132, s54, v48
	v_mul_f32_e32 v133, s54, v49
	v_mul_f32_e32 v142, s54, v46
	v_mul_f32_e32 v143, s54, v47
	v_mul_f32_e32 v140, s54, v44
	v_mul_f32_e32 v141, s54, v45

; __device__ __forceinline__ f32x4 silu4(f32x4 v) { return v * sigm4(v); }
; __device__ __forceinline__ u32x4 pack8(f32x4 v0, f32x4 v1) { u32x4 w; w.x = cvt_pk_bf16(v0[0], v0[1]); w.y = cvt_pk_bf16(v0[2], v0[3]); w.z = cvt_pk_bf16(v1[0], v1[1]); w.w = cvt_pk_bf16(v1[2], v1[3]); return w; }
;     __device__ __forceinline__ void store_rows(const f32x4& a0, const f32x4& a1, const f32x4& b0, const f32x4& b1, int type, bf16_t* base, size_t off) const {
;         f32x4 x0 = a0, x1 = a1, y0 = b0, y1 = b1;
;         if (type == 1) { x0 = x0 * 0.0625f; x1 = x1 * 0.0625f; y0 = y0 * 0.0625f; y1 = y1 * 0.0625f; }
;         if (type == 3) { x0 = silu4(x0); x1 = silu4(x1); y0 = silu4(y0); y1 = silu4(y1); }
;         st16(base, off, pack8(x0, x1));
;         st16(base, off + HALF, pack8(y0, y1));
.LBB0_677:
	v_add_u32_e32 v3, 0x90000, v0
	v_cvt_pk_bf16_f32 v136, v136, v137
	v_cvt_pk_bf16_f32 v137, v138, v139
	v_cvt_pk_bf16_f32 v138, v144, v145
	v_and_b32_e32 v144, -2, v3
	v_mov_b32_e32 v145, v1
	v_lshl_add_u64 v[144:145], s[30:31], 0, v[144:145]
	v_add_u32_e32 v3, 0x90100, v0
	v_cvt_pk_bf16_f32 v139, v146, v147
	global_store_dwordx4 v[144:145], v[136:139], off
	v_cvt_pk_bf16_f32 v132, v132, v133
	v_cvt_pk_bf16_f32 v133, v134, v135
	v_cvt_pk_bf16_f32 v134, v140, v141
	v_cvt_pk_bf16_f32 v135, v142, v143
	v_and_b32_e32 v3, -2, v3
	global_store_dwordx4 v3, v[132:135], s[30:31]
	v_mov_b64_e32 v[138:139], v[26:27]
	v_mov_b64_e32 v[146:147], v[22:23]
	v_mov_b64_e32 v[134:135], v[34:35]
	v_mov_b64_e32 v[142:143], v[30:31]
	s_and_b64 vcc, exec, s[6:7]
	v_mov_b64_e32 v[136:137], v[24:25]
	v_mov_b64_e32 v[144:145], v[20:21]
	v_mov_b64_e32 v[132:133], v[32:33]
	v_mov_b64_e32 v[140:141], v[28:29]
	s_cbranch_vccnz .LBB0_679
	v_mul_f32_e32 v138, s54, v26
	v_mul_f32_e32 v139, s54, v27
	v_mul_f32_e32 v136, s54, v24
	v_mul_f32_e32 v137, s54, v25
	v_mul_f32_e32 v146, s54, v22
	v_mul_f32_e32 v147, s54, v23
	v_mul_f32_e32 v144, s54, v20
	v_mul_f32_e32 v145, s54, v21
	v_mul_f32_e32 v134, s54, v34
	v_mul_f32_e32 v135, s54, v35
	v_mul_f32_e32 v132, s54, v32
	v_mul_f32_e32 v133, s54, v33
	v_mul_f32_e32 v142, s54, v30
	v_mul_f32_e32 v143, s54, v31
	v_mul_f32_e32 v140, s54, v28
	v_mul_f32_e32 v141, s54, v29

; __device__ __forceinline__ f32x4 silu4(f32x4 v) { return v * sigm4(v); }
; __device__ __forceinline__ u32x4 pack8(f32x4 v0, f32x4 v1) { u32x4 w; w.x = cvt_pk_bf16(v0[0], v0[1]); w.y = cvt_pk_bf16(v0[2], v0[3]); w.z = cvt_pk_bf16(v1[0], v1[1]); w.w = cvt_pk_bf16(v1[2], v1[3]); return w; }
;     __device__ __forceinline__ void store_rows(const f32x4& a0, const f32x4& a1, const f32x4& b0, const f32x4& b1, int type, bf16_t* base, size_t off) const {
;         f32x4 x0 = a0, x1 = a1, y0 = b0, y1 = b1;
;         if (type == 1) { x0 = x0 * 0.0625f; x1 = x1 * 0.0625f; y0 = y0 * 0.0625f; y1 = y1 * 0.0625f; }
;         if (type == 3) { x0 = silu4(x0); x1 = silu4(x1); y0 = silu4(y0); y1 = silu4(y1); }
;         st16(base, off, pack8(x0, x1));
;         st16(base, off + HALF, pack8(y0, y1));
.LBB0_681:
	v_add_u32_e32 v3, 0xa0000, v0
	v_cvt_pk_bf16_f32 v136, v136, v137
	v_cvt_pk_bf16_f32 v137, v138, v139
	v_cvt_pk_bf16_f32 v138, v144, v145
	v_and_b32_e32 v144, -2, v3
	v_mov_b32_e32 v145, v1
	v_lshl_add_u64 v[144:145], s[30:31], 0, v[144:145]
	v_add_u32_e32 v0, 0xa0100, v0
	v_cvt_pk_bf16_f32 v139, v146, v147
	global_store_dwordx4 v[144:145], v[136:139], off
	v_cvt_pk_bf16_f32 v132, v132, v133
	v_cvt_pk_bf16_f32 v133, v134, v135
	v_cvt_pk_bf16_f32 v134, v140, v141
	v_cvt_pk_bf16_f32 v135, v142, v143
	v_and_b32_e32 v0, -2, v0
	global_store_dwordx4 v0, v[132:135], s[30:31]
	v_mov_b64_e32 v[138:139], v[10:11]
	v_mov_b64_e32 v[146:147], v[6:7]
	v_mov_b64_e32 v[134:135], v[18:19]
	v_mov_b64_e32 v[142:143], v[14:15]
	s_and_b64 vcc, exec, s[6:7]
	v_mov_b64_e32 v[136:137], v[8:9]
	v_mov_b64_e32 v[144:145], v[4:5]
	v_mov_b64_e32 v[132:133], v[16:17]
	v_mov_b64_e32 v[140:141], v[12:13]
	s_cbranch_vccnz .LBB0_683
	v_mul_f32_e32 v138, s54, v10
	v_mul_f32_e32 v139, s54, v11
	v_mul_f32_e32 v136, s54, v8
	v_mul_f32_e32 v137, s54, v9
	v_mul_f32_e32 v146, s54, v6
	v_mul_f32_e32 v147, s54, v7
	v_mul_f32_e32 v144, s54, v4
	v_mul_f32_e32 v145, s54, v5
	v_mul_f32_e32 v134, s54, v18
	v_mul_f32_e32 v135, s54, v19
	v_mul_f32_e32 v132, s54, v16
	v_mul_f32_e32 v133, s54, v17
	v_mul_f32_e32 v142, s54, v14
	v_mul_f32_e32 v143, s54, v15
	v_mul_f32_e32 v140, s54, v12
	v_mul_f32_e32 v141, s54, v13

; #define PG8_GAS __attribute__((address_space(1)))
; __device__ __forceinline__ f32x4 silu4(f32x4 v) { return v * sigm4(v); }
; __device__ __forceinline__ u32x4 pack8(f32x4 v0, f32x4 v1) { u32x4 w; w.x = cvt_pk_bf16(v0[0], v0[1]); w.y = cvt_pk_bf16(v0[2], v0[3]); w.z = cvt_pk_bf16(v1[0], v1[1]); w.w = cvt_pk_bf16(v1[2], v1[3]); return w; }
;     __device__ __forceinline__ void store_rows(const f32x4& a0, const f32x4& a1, const f32x4& b0, const f32x4& b1, int type, bf16_t* base, size_t off) const {
;         f32x4 x0 = a0, x1 = a1, y0 = b0, y1 = b1;
;         if (type == 1) { x0 = x0 * 0.0625f; x1 = x1 * 0.0625f; y0 = y0 * 0.0625f; y1 = y1 * 0.0625f; }
;         if (type == 3) { x0 = silu4(x0); x1 = silu4(x1); y0 = silu4(y0); y1 = silu4(y1); }
;         st16(base, off, pack8(x0, x1));
;         st16(base, off + HALF, pack8(y0, y1));
;     __device__ __forceinline__ void operator()(const f32x4 (&acc)[2][2][4][2], const Unit& u, int wr, int wc, int fr_in, int fq_in) const {
;     ...
;             for (int m = 0; m < 4; ++m) {
;                 const int pos = 16 * m + fr;
;                 const f32x4 c0 = *(const PG8_GAS f32x4*)(cosT + pos * 64 + fidx), c1 = *(const PG8_GAS f32x4*)(cosT + pos * 64 + fidx + 4), s0 = *(const PG8_GAS f32x4*)(sinT + pos * 64 + fidx), s1 = *(const PG8_GAS f32x4*)(sinT + pos * 64 + fidx + 4);
; #pragma unroll
;                 for (int ai = 0; ai < 2; ++ai) { const f32x4 a0 = acc[ai][0][m][0], a1 = acc[ai][0][m][1], b0 = acc[ai][1][m][0], b1 = acc[ai][1][m][1];
;                     store_rows(a0 * c0 - b0 * s0, a1 * c1 - b1 * s1, a0 * s0 + b0 * c0, a1 * s1 + b1 * c1, type, base, (size_t)(row0 + ai * HALF + m * 16) * 2048 + coff); }
;             }
.LBB0_686:
	s_and_b64 vcc, exec, s[6:7]
	s_cbranch_vccz .LBB0_723
	v_add_u32_e32 v132, s51, v153
	v_ashrrev_i32_e32 v133, 31, v132
	s_cmp_eq_u32 s23, 1
	s_cselect_b64 s[8:9], -1, 0
	v_lshlrev_b64 v[148:149], 1, v[148:149]
	s_mov_b64 s[6:7], -1
	s_andn2_b64 vcc, exec, s[18:19]
	v_lshlrev_b64 v[150:151], 2, v[132:133]
	s_cbranch_vccnz .LBB0_705
	v_lshlrev_b32_e32 v152, 6, v152
	v_ashrrev_i32_e32 v153, 31, v152
	v_lshlrev_b64 v[132:133], 2, v[152:153]
	v_lshl_add_u64 v[134:135], s[12:13], 0, v[132:133]
	v_lshl_add_u64 v[134:135], v[134:135], 0, v[150:151]
	v_lshl_add_u64 v[132:133], s[14:15], 0, v[132:133]
	global_load_dwordx4 v[140:143], v[134:135], off
	global_load_dwordx4 v[136:139], v[134:135], off offset:16
	v_lshl_add_u64 v[132:133], v[132:133], 0, v[150:151]
	global_load_dwordx4 v[144:147], v[132:133], off
	s_nop 0
	global_load_dwordx4 v[132:135], v[132:133], off offset:16
	v_add_u32_e32 v240, 0x400, v152
	v_ashrrev_i32_e32 v241, 31, v240
	v_lshlrev_b64 v[240:241], 2, v[240:241]
	v_lshl_add_u64 v[242:243], s[12:13], 0, v[240:241]
	v_lshl_add_u64 v[242:243], v[242:243], 0, v[150:151]
	v_lshl_add_u64 v[240:241], s[14:15], 0, v[240:241]
	v_lshl_add_u64 v[240:241], v[240:241], 0, v[150:151]
	global_load_dwordx4 v[200:203], v[242:243], off
	global_load_dwordx4 v[196:199], v[242:243], off offset:16
	global_load_dwordx4 v[204:207], v[240:241], off
	global_load_dwordx4 v[192:195], v[240:241], off offset:16
	v_add_u32_e32 v240, 0x800, v152
	v_ashrrev_i32_e32 v241, 31, v240
	v_lshlrev_b64 v[240:241], 2, v[240:241]
	v_lshl_add_u64 v[242:243], s[12:13], 0, v[240:241]
	v_lshl_add_u64 v[242:243], v[242:243], 0, v[150:151]
	v_lshl_add_u64 v[240:241], s[14:15], 0, v[240:241]
	v_lshl_add_u64 v[240:241], v[240:241], 0, v[150:151]
	global_load_dwordx4 v[216:219], v[242:243], off
	global_load_dwordx4 v[212:215], v[242:243], off offset:16
	global_load_dwordx4 v[220:223], v[240:241], off
	global_load_dwordx4 v[208:211], v[240:241], off offset:16
	v_add_u32_e32 v240, 0xc00, v152
	v_ashrrev_i32_e32 v241, 31, v240
	v_lshlrev_b64 v[240:241], 2, v[240:241]
	v_lshl_add_u64 v[242:243], s[12:13], 0, v[240:241]
	v_lshl_add_u64 v[242:243], v[242:243], 0, v[150:151]
	v_lshl_add_u64 v[240:241], s[14:15], 0, v[240:241]
	v_lshl_add_u64 v[240:241], v[240:241], 0, v[150:151]
	global_load_dwordx4 v[232:235], v[242:243], off
	global_load_dwordx4 v[228:231], v[242:243], off offset:16
	global_load_dwordx4 v[236:239], v[240:241], off
	global_load_dwordx4 v[224:227], v[240:241], off offset:16
	s_and_b64 vcc, exec, s[8:9]
	s_waitcnt vmcnt(15)
	v_mul_f32_e32 v154, v130, v142
	v_mul_f32_e32 v155, v131, v143
	v_mul_f32_e32 v156, v128, v140
	v_mul_f32_e32 v157, v129, v141
	s_waitcnt vmcnt(14)
	v_mul_f32_e32 v158, v126, v138
	v_mul_f32_e32 v159, v127, v139
	v_mul_f32_e32 v160, v124, v136
	v_mul_f32_e32 v161, v125, v137
	v_mul_f32_e32 v178, v122, v142
	v_mul_f32_e32 v179, v123, v143
	v_mul_f32_e32 v180, v120, v140
	v_mul_f32_e32 v181, v121, v141
	v_mul_f32_e32 v188, v118, v138
	v_mul_f32_e32 v189, v119, v139
	v_mul_f32_e32 v190, v116, v136
	v_mul_f32_e32 v191, v117, v137
	s_waitcnt vmcnt(13)
	v_fma_f32 v166, v122, v146, -v154
	v_fma_f32 v167, v123, v147, -v155
	v_fma_f32 v168, v120, v144, -v156
	v_fma_f32 v169, v121, v145, -v157
	s_waitcnt vmcnt(12)
	v_fma_f32 v162, v118, v134, -v158
	v_fma_f32 v163, v119, v135, -v159
	v_fma_f32 v164, v116, v132, -v160
	v_fma_f32 v165, v117, v133, -v161
	v_fma_f32 v158, v130, v146, v178
	v_fma_f32 v159, v131, v147, v179
	v_fma_f32 v160, v128, v144, v180
	v_fma_f32 v161, v129, v145, v181
	v_fma_f32 v154, v126, v134, v188
	v_fma_f32 v155, v127, v135, v189
	v_fma_f32 v156, v124, v132, v190
	v_fma_f32 v157, v125, v133, v191
	s_cbranch_vccz .LBB0_690
	v_mul_f32_e32 v166, s54, v166
	v_mul_f32_e32 v167, s54, v167
	v_mul_f32_e32 v168, s54, v168
	v_mul_f32_e32 v169, s54, v169
	v_mul_f32_e32 v162, s54, v162
	v_mul_f32_e32 v163, s54, v163
	v_mul_f32_e32 v164, s54, v164
	v_mul_f32_e32 v165, s54, v165
	v_mul_f32_e32 v158, s54, v158
	v_mul_f32_e32 v159, s54, v159
	v_mul_f32_e32 v160, s54, v160
	v_mul_f32_e32 v161, s54, v161
	v_mul_f32_e32 v154, s54, v154
	v_mul_f32_e32 v155, s54, v155
	v_mul_f32_e32 v156, s54, v156
	v_mul_f32_e32 v157, s54, v157
.LBB0_690:
	v_lshl_add_u32 v3, v2, 12, v148
	v_and_b32_e32 v0, -2, v3
	v_cvt_pk_bf16_f32 v188, v168, v169
	v_cvt_pk_bf16_f32 v189, v166, v167
	v_cvt_pk_bf16_f32 v190, v164, v165
	v_cvt_pk_bf16_f32 v191, v162, v163
	v_lshl_add_u64 v[162:163], s[30:31], 0, v[0:1]
	v_add_u32_e32 v0, 0x100, v3
	global_store_dwordx4 v[162:163], v[188:191], off
	v_cvt_pk_bf16_f32 v160, v160, v161
	v_cvt_pk_bf16_f32 v161, v158, v159
	v_cvt_pk_bf16_f32 v162, v156, v157
	v_cvt_pk_bf16_f32 v163, v154, v155
	v_and_b32_e32 v0, -2, v0
	global_store_dwordx4 v0, v[160:163], s[30:31]
	v_mul_f32_e32 v154, v66, v142
	v_mul_f32_e32 v155, v67, v143
	v_mul_f32_e32 v156, v64, v140
	v_mul_f32_e32 v157, v65, v141
	v_mul_f32_e32 v158, v62, v138
	v_mul_f32_e32 v159, v63, v139
	v_mul_f32_e32 v160, v60, v136
	v_mul_f32_e32 v161, v61, v137
	v_mul_f32_e32 v142, v58, v142
	v_mul_f32_e32 v143, v59, v143
	v_mul_f32_e32 v162, v56, v140
	v_mul_f32_e32 v163, v57, v141
	v_mul_f32_e32 v138, v54, v138
	v_mul_f32_e32 v139, v55, v139
	v_mul_f32_e32 v136, v52, v136
	v_mul_f32_e32 v137, v53, v137
	v_cndmask_b32_e64 v0, 0, 1, s[8:9]
	v_fma_f32 v154, v58, v146, -v154
	v_fma_f32 v155, v59, v147, -v155
	v_fma_f32 v156, v56, v144, -v156
	v_fma_f32 v157, v57, v145, -v157
	v_fma_f32 v158, v54, v134, -v158
	v_fma_f32 v159, v55, v135, -v159
	v_fma_f32 v160, v52, v132, -v160
	v_fma_f32 v161, v53, v133, -v161
	v_fma_f32 v140, v66, v146, v142
	v_fma_f32 v141, v67, v147, v143
	v_fma_f32 v142, v64, v144, v162
	v_fma_f32 v143, v65, v145, v163
	v_fma_f32 v134, v62, v134, v138
	v_fma_f32 v135, v63, v135, v139
	v_cmp_ne_u32_e64 s[6:7], 1, v0
	s_andn2_b64 vcc, exec, s[8:9]
	v_fma_f32 v132, v60, v132, v136
	v_fma_f32 v133, v61, v133, v137
	s_cbranch_vccnz .LBB0_692
	v_mul_f32_e32 v154, s54, v154
	v_mul_f32_e32 v155, s54, v155
	v_mul_f32_e32 v156, s54, v156
	v_mul_f32_e32 v157, s54, v157
	v_mul_f32_e32 v158, s54, v158
	v_mul_f32_e32 v159, s54, v159
	v_mul_f32_e32 v160, s54, v160
	v_mul_f32_e32 v161, s54, v161
	v_mul_f32_e32 v140, s54, v140
	v_mul_f32_e32 v141, s54, v141
	v_mul_f32_e32 v142, s54, v142
	v_mul_f32_e32 v143, s54, v143
	v_mul_f32_e32 v134, s54, v134
	v_mul_f32_e32 v135, s54, v135
	v_mul_f32_e32 v132, s54, v132
	v_mul_f32_e32 v133, s54, v133
; #define PG8_GAS __attribute__((address_space(1)))
; __device__ __forceinline__ f32x4 silu4(f32x4 v) { return v * sigm4(v); }
; __device__ __forceinline__ u32x4 pack8(f32x4 v0, f32x4 v1) { u32x4 w; w.x = cvt_pk_bf16(v0[0], v0[1]); w.y = cvt_pk_bf16(v0[2], v0[3]); w.z = cvt_pk_bf16(v1[0], v1[1]); w.w = cvt_pk_bf16(v1[2], v1[3]); return w; }
;     __device__ __forceinline__ void store_rows(const f32x4& a0, const f32x4& a1, const f32x4& b0, const f32x4& b1, int type, bf16_t* base, size_t off) const {
;         f32x4 x0 = a0, x1 = a1, y0 = b0, y1 = b1;
;         if (type == 1) { x0 = x0 * 0.0625f; x1 = x1 * 0.0625f; y0 = y0 * 0.0625f; y1 = y1 * 0.0625f; }
;         if (type == 3) { x0 = silu4(x0); x1 = silu4(x1); y0 = silu4(y0); y1 = silu4(y1); }
;         st16(base, off, pack8(x0, x1));
;         st16(base, off + HALF, pack8(y0, y1));
;     __device__ __forceinline__ void operator()(const f32x4 (&acc)[2][2][4][2], const Unit& u, int wr, int wc, int fr_in, int fq_in) const {
;     ...
;             for (int m = 0; m < 4; ++m) {
;                 const int pos = 16 * m + fr;
;                 const f32x4 c0 = *(const PG8_GAS f32x4*)(cosT + pos * 64 + fidx), c1 = *(const PG8_GAS f32x4*)(cosT + pos * 64 + fidx + 4), s0 = *(const PG8_GAS f32x4*)(sinT + pos * 64 + fidx), s1 = *(const PG8_GAS f32x4*)(sinT + pos * 64 + fidx + 4);
; #pragma unroll
;                 for (int ai = 0; ai < 2; ++ai) { const f32x4 a0 = acc[ai][0][m][0], a1 = acc[ai][0][m][1], b0 = acc[ai][1][m][0], b1 = acc[ai][1][m][1];
;                     store_rows(a0 * c0 - b0 * s0, a1 * c1 - b1 * s1, a0 * s0 + b0 * c0, a1 * s1 + b1 * c1, type, base, (size_t)(row0 + ai * HALF + m * 16) * 2048 + coff); }
;             }
.LBB0_692:
	v_add_u32_e32 v0, 0x80000, v3
	v_and_b32_e32 v0, -2, v0
	v_cvt_pk_bf16_f32 v136, v156, v157
	v_cvt_pk_bf16_f32 v137, v154, v155
	v_cvt_pk_bf16_f32 v138, v160, v161
	v_lshl_add_u64 v[144:145], s[30:31], 0, v[0:1]
	v_cvt_pk_bf16_f32 v139, v158, v159
	global_store_dwordx4 v[144:145], v[136:139], off
	v_add_u32_e32 v0, 0x80100, v3
	v_and_b32_e32 v0, -2, v0
	v_cvt_pk_bf16_f32 v136, v142, v143
	v_cvt_pk_bf16_f32 v137, v140, v141
	v_cvt_pk_bf16_f32 v138, v132, v133
	v_cvt_pk_bf16_f32 v139, v134, v135
	global_store_dwordx4 v0, v[136:139], s[30:31]
	s_and_b64 vcc, exec, s[6:7]
	s_waitcnt vmcnt(15)
	v_mul_f32_e32 v154, v114, v202
	v_mul_f32_e32 v155, v115, v203
	v_mul_f32_e32 v156, v112, v200
	v_mul_f32_e32 v157, v113, v201
	s_waitcnt vmcnt(14)
	v_mul_f32_e32 v158, v110, v198
	v_mul_f32_e32 v159, v111, v199
	v_mul_f32_e32 v160, v108, v196
	v_mul_f32_e32 v161, v109, v197
	v_mul_f32_e32 v178, v106, v202
	v_mul_f32_e32 v179, v107, v203
	v_mul_f32_e32 v180, v104, v200
	v_mul_f32_e32 v181, v105, v201
	v_mul_f32_e32 v188, v102, v198
	v_mul_f32_e32 v189, v103, v199
	v_mul_f32_e32 v190, v100, v196
	v_mul_f32_e32 v191, v101, v197
	s_waitcnt vmcnt(13)
	v_fma_f32 v166, v106, v206, -v154
	v_fma_f32 v167, v107, v207, -v155
	v_fma_f32 v168, v104, v204, -v156
	v_fma_f32 v169, v105, v205, -v157
	s_waitcnt vmcnt(12)
	v_fma_f32 v162, v102, v194, -v158
	v_fma_f32 v163, v103, v195, -v159
	v_fma_f32 v164, v100, v192, -v160
	v_fma_f32 v165, v101, v193, -v161
	v_fma_f32 v158, v114, v206, v178
	v_fma_f32 v159, v115, v207, v179
	v_fma_f32 v160, v112, v204, v180
	v_fma_f32 v161, v113, v205, v181
	v_fma_f32 v154, v110, v194, v188
	v_fma_f32 v155, v111, v195, v189
	v_fma_f32 v156, v108, v192, v190
	v_fma_f32 v157, v109, v193, v191
	s_cbranch_vccnz .LBB0_694
	v_mul_f32_e32 v166, s54, v166
	v_mul_f32_e32 v167, s54, v167
	v_mul_f32_e32 v168, s54, v168
	v_mul_f32_e32 v169, s54, v169
	v_mul_f32_e32 v162, s54, v162
	v_mul_f32_e32 v163, s54, v163
	v_mul_f32_e32 v164, s54, v164
	v_mul_f32_e32 v165, s54, v165
	v_mul_f32_e32 v158, s54, v158
	v_mul_f32_e32 v159, s54, v159
	v_mul_f32_e32 v160, s54, v160
	v_mul_f32_e32 v161, s54, v161
	v_mul_f32_e32 v154, s54, v154
	v_mul_f32_e32 v155, s54, v155
	v_mul_f32_e32 v156, s54, v156
	v_mul_f32_e32 v157, s54, v157
.LBB0_694:
	v_add_u32_e32 v0, 0x10000, v3
	v_and_b32_e32 v0, -2, v0
	v_cvt_pk_bf16_f32 v188, v168, v169
	v_cvt_pk_bf16_f32 v189, v166, v167
	v_cvt_pk_bf16_f32 v190, v164, v165
	v_cvt_pk_bf16_f32 v191, v162, v163
	v_lshl_add_u64 v[162:163], s[30:31], 0, v[0:1]
	v_add_u32_e32 v0, 0x10100, v3
	global_store_dwordx4 v[162:163], v[188:191], off
	v_cvt_pk_bf16_f32 v160, v160, v161
	v_cvt_pk_bf16_f32 v161, v158, v159
	v_cvt_pk_bf16_f32 v162, v156, v157
	v_cvt_pk_bf16_f32 v163, v154, v155
	v_and_b32_e32 v0, -2, v0
	global_store_dwordx4 v0, v[160:163], s[30:31]
	v_mul_f32_e32 v154, v50, v202
	v_mul_f32_e32 v155, v51, v203
	v_mul_f32_e32 v156, v48, v200
	v_mul_f32_e32 v157, v49, v201
	v_mul_f32_e32 v158, v46, v198
	v_mul_f32_e32 v159, v47, v199
	v_mul_f32_e32 v160, v44, v196
	v_mul_f32_e32 v161, v45, v197
	v_mul_f32_e32 v142, v42, v202
	v_mul_f32_e32 v143, v43, v203
	v_mul_f32_e32 v162, v40, v200
	v_mul_f32_e32 v163, v41, v201
	v_mul_f32_e32 v138, v38, v198
	v_mul_f32_e32 v139, v39, v199
	v_mul_f32_e32 v136, v36, v196
	v_mul_f32_e32 v137, v37, v197
	v_fma_f32 v154, v42, v206, -v154
	v_fma_f32 v155, v43, v207, -v155
	v_fma_f32 v156, v40, v204, -v156
	v_fma_f32 v157, v41, v205, -v157
	v_fma_f32 v158, v38, v194, -v158
	v_fma_f32 v159, v39, v195, -v159
	v_fma_f32 v160, v36, v192, -v160
	v_fma_f32 v161, v37, v193, -v161
	v_fma_f32 v140, v50, v206, v142
	v_fma_f32 v141, v51, v207, v143
	v_fma_f32 v142, v48, v204, v162
	v_fma_f32 v143, v49, v205, v163
	v_fma_f32 v134, v46, v194, v138
	v_fma_f32 v135, v47, v195, v139
	s_and_b64 vcc, exec, s[6:7]
	v_fma_f32 v132, v44, v192, v136
	v_fma_f32 v133, v45, v193, v137
	s_cbranch_vccnz .LBB0_696
	v_mul_f32_e32 v154, s54, v154
	v_mul_f32_e32 v155, s54, v155
	v_mul_f32_e32 v156, s54, v156
	v_mul_f32_e32 v157, s54, v157
	v_mul_f32_e32 v158, s54, v158
	v_mul_f32_e32 v159, s54, v159
	v_mul_f32_e32 v160, s54, v160
	v_mul_f32_e32 v161, s54, v161
	v_mul_f32_e32 v140, s54, v140
	v_mul_f32_e32 v141, s54, v141
	v_mul_f32_e32 v142, s54, v142
	v_mul_f32_e32 v143, s54, v143
	v_mul_f32_e32 v134, s54, v134
	v_mul_f32_e32 v135, s54, v135
	v_mul_f32_e32 v132, s54, v132
	v_mul_f32_e32 v133, s54, v133
.LBB0_696:
	v_add_u32_e32 v0, 0x90000, v3
	v_and_b32_e32 v0, -2, v0
	v_cvt_pk_bf16_f32 v136, v156, v157
	v_cvt_pk_bf16_f32 v137, v154, v155
	v_cvt_pk_bf16_f32 v138, v160, v161
	v_lshl_add_u64 v[144:145], s[30:31], 0, v[0:1]
	v_cvt_pk_bf16_f32 v139, v158, v159
	global_store_dwordx4 v[144:145], v[136:139], off
	v_add_u32_e32 v0, 0x90100, v3
	v_and_b32_e32 v0, -2, v0
	v_cvt_pk_bf16_f32 v136, v142, v143
	v_cvt_pk_bf16_f32 v137, v140, v141
	v_cvt_pk_bf16_f32 v138, v132, v133
	v_cvt_pk_bf16_f32 v139, v134, v135
	global_store_dwordx4 v0, v[136:139], s[30:31]
	s_and_b64 vcc, exec, s[6:7]
	s_waitcnt vmcnt(15)
	v_mul_f32_e32 v154, v98, v218
	v_mul_f32_e32 v155, v99, v219
	v_mul_f32_e32 v156, v96, v216
	v_mul_f32_e32 v157, v97, v217
	s_waitcnt vmcnt(14)
	v_mul_f32_e32 v158, v94, v214
	v_mul_f32_e32 v159, v95, v215
	v_mul_f32_e32 v160, v92, v212
	v_mul_f32_e32 v161, v93, v213
	v_mul_f32_e32 v178, v90, v218
	v_mul_f32_e32 v179, v91, v219
	v_mul_f32_e32 v180, v88, v216
	v_mul_f32_e32 v181, v89, v217
	v_mul_f32_e32 v188, v86, v214
	v_mul_f32_e32 v189, v87, v215
	v_mul_f32_e32 v190, v84, v212
	v_mul_f32_e32 v191, v85, v213
	s_waitcnt vmcnt(13)
	v_fma_f32 v166, v90, v222, -v154
	v_fma_f32 v167, v91, v223, -v155
	v_fma_f32 v168, v88, v220, -v156
	v_fma_f32 v169, v89, v221, -v157
	s_waitcnt vmcnt(12)
	v_fma_f32 v162, v86, v210, -v158
	v_fma_f32 v163, v87, v211, -v159
	v_fma_f32 v164, v84, v208, -v160
	v_fma_f32 v165, v85, v209, -v161
	v_fma_f32 v158, v98, v222, v178
	v_fma_f32 v159, v99, v223, v179
	v_fma_f32 v160, v96, v220, v180
	v_fma_f32 v161, v97, v221, v181
	v_fma_f32 v154, v94, v210, v188
	v_fma_f32 v155, v95, v211, v189
	v_fma_f32 v156, v92, v208, v190
	v_fma_f32 v157, v93, v209, v191
	s_cbranch_vccnz .LBB0_698
	v_mul_f32_e32 v166, s54, v166
	v_mul_f32_e32 v167, s54, v167
	v_mul_f32_e32 v168, s54, v168
	v_mul_f32_e32 v169, s54, v169
	v_mul_f32_e32 v162, s54, v162
	v_mul_f32_e32 v163, s54, v163
	v_mul_f32_e32 v164, s54, v164
	v_mul_f32_e32 v165, s54, v165
	v_mul_f32_e32 v158, s54, v158
	v_mul_f32_e32 v159, s54, v159
	v_mul_f32_e32 v160, s54, v160
	v_mul_f32_e32 v161, s54, v161
	v_mul_f32_e32 v154, s54, v154
	v_mul_f32_e32 v155, s54, v155
	v_mul_f32_e32 v156, s54, v156
	v_mul_f32_e32 v157, s54, v157
; #define PG8_GAS __attribute__((address_space(1)))
; __device__ __forceinline__ f32x4 silu4(f32x4 v) { return v * sigm4(v); }
; __device__ __forceinline__ u32x4 pack8(f32x4 v0, f32x4 v1) { u32x4 w; w.x = cvt_pk_bf16(v0[0], v0[1]); w.y = cvt_pk_bf16(v0[2], v0[3]); w.z = cvt_pk_bf16(v1[0], v1[1]); w.w = cvt_pk_bf16(v1[2], v1[3]); return w; }
;     __device__ __forceinline__ void store_rows(const f32x4& a0, const f32x4& a1, const f32x4& b0, const f32x4& b1, int type, bf16_t* base, size_t off) const {
;         f32x4 x0 = a0, x1 = a1, y0 = b0, y1 = b1;
;         if (type == 1) { x0 = x0 * 0.0625f; x1 = x1 * 0.0625f; y0 = y0 * 0.0625f; y1 = y1 * 0.0625f; }
;         if (type == 3) { x0 = silu4(x0); x1 = silu4(x1); y0 = silu4(y0); y1 = silu4(y1); }
;         st16(base, off, pack8(x0, x1));
;         st16(base, off + HALF, pack8(y0, y1));
;     __device__ __forceinline__ void operator()(const f32x4 (&acc)[2][2][4][2], const Unit& u, int wr, int wc, int fr_in, int fq_in) const {
;     ...
;             for (int m = 0; m < 4; ++m) {
;                 const int pos = 16 * m + fr;
;                 const f32x4 c0 = *(const PG8_GAS f32x4*)(cosT + pos * 64 + fidx), c1 = *(const PG8_GAS f32x4*)(cosT + pos * 64 + fidx + 4), s0 = *(const PG8_GAS f32x4*)(sinT + pos * 64 + fidx), s1 = *(const PG8_GAS f32x4*)(sinT + pos * 64 + fidx + 4);
; #pragma unroll
;                 for (int ai = 0; ai < 2; ++ai) { const f32x4 a0 = acc[ai][0][m][0], a1 = acc[ai][0][m][1], b0 = acc[ai][1][m][0], b1 = acc[ai][1][m][1];
;                     store_rows(a0 * c0 - b0 * s0, a1 * c1 - b1 * s1, a0 * s0 + b0 * c0, a1 * s1 + b1 * c1, type, base, (size_t)(row0 + ai * HALF + m * 16) * 2048 + coff); }
;             }
.LBB0_698:
	v_add_u32_e32 v0, 0x20000, v3
	v_and_b32_e32 v0, -2, v0
	v_cvt_pk_bf16_f32 v188, v168, v169
	v_cvt_pk_bf16_f32 v189, v166, v167
	v_cvt_pk_bf16_f32 v190, v164, v165
	v_cvt_pk_bf16_f32 v191, v162, v163
	v_lshl_add_u64 v[162:163], s[30:31], 0, v[0:1]
	v_add_u32_e32 v0, 0x20100, v3
	global_store_dwordx4 v[162:163], v[188:191], off
	v_cvt_pk_bf16_f32 v160, v160, v161
	v_cvt_pk_bf16_f32 v161, v158, v159
	v_cvt_pk_bf16_f32 v162, v156, v157
	v_cvt_pk_bf16_f32 v163, v154, v155
	v_and_b32_e32 v0, -2, v0
	global_store_dwordx4 v0, v[160:163], s[30:31]
	v_mul_f32_e32 v154, v34, v218
	v_mul_f32_e32 v155, v35, v219
	v_mul_f32_e32 v156, v32, v216
	v_mul_f32_e32 v157, v33, v217
	v_mul_f32_e32 v158, v30, v214
	v_mul_f32_e32 v159, v31, v215
	v_mul_f32_e32 v160, v28, v212
	v_mul_f32_e32 v161, v29, v213
	v_mul_f32_e32 v142, v26, v218
	v_mul_f32_e32 v143, v27, v219
	v_mul_f32_e32 v162, v24, v216
	v_mul_f32_e32 v163, v25, v217
	v_mul_f32_e32 v138, v22, v214
	v_mul_f32_e32 v139, v23, v215
	v_mul_f32_e32 v136, v20, v212
	v_mul_f32_e32 v137, v21, v213
	v_fma_f32 v154, v26, v222, -v154
	v_fma_f32 v155, v27, v223, -v155
	v_fma_f32 v156, v24, v220, -v156
	v_fma_f32 v157, v25, v221, -v157
	v_fma_f32 v158, v22, v210, -v158
	v_fma_f32 v159, v23, v211, -v159
	v_fma_f32 v160, v20, v208, -v160
	v_fma_f32 v161, v21, v209, -v161
	v_fma_f32 v140, v34, v222, v142
	v_fma_f32 v141, v35, v223, v143
	v_fma_f32 v142, v32, v220, v162
	v_fma_f32 v143, v33, v221, v163
	v_fma_f32 v134, v30, v210, v138
	v_fma_f32 v135, v31, v211, v139
	s_and_b64 vcc, exec, s[6:7]
	v_fma_f32 v132, v28, v208, v136
	v_fma_f32 v133, v29, v209, v137
	s_cbranch_vccnz .LBB0_700
	v_mul_f32_e32 v154, s54, v154
	v_mul_f32_e32 v155, s54, v155
	v_mul_f32_e32 v156, s54, v156
	v_mul_f32_e32 v157, s54, v157
	v_mul_f32_e32 v158, s54, v158
	v_mul_f32_e32 v159, s54, v159
	v_mul_f32_e32 v160, s54, v160
	v_mul_f32_e32 v161, s54, v161
	v_mul_f32_e32 v140, s54, v140
	v_mul_f32_e32 v141, s54, v141
	v_mul_f32_e32 v142, s54, v142
	v_mul_f32_e32 v143, s54, v143
	v_mul_f32_e32 v134, s54, v134
	v_mul_f32_e32 v135, s54, v135
	v_mul_f32_e32 v132, s54, v132
	v_mul_f32_e32 v133, s54, v133
.LBB0_700:
	v_add_u32_e32 v0, 0xa0000, v3
	v_and_b32_e32 v0, -2, v0
	v_cvt_pk_bf16_f32 v136, v156, v157
	v_cvt_pk_bf16_f32 v137, v154, v155
	v_cvt_pk_bf16_f32 v138, v160, v161
	v_lshl_add_u64 v[144:145], s[30:31], 0, v[0:1]
	v_cvt_pk_bf16_f32 v139, v158, v159
	global_store_dwordx4 v[144:145], v[136:139], off
	v_add_u32_e32 v0, 0xa0100, v3
	v_and_b32_e32 v0, -2, v0
	v_cvt_pk_bf16_f32 v136, v142, v143
	v_cvt_pk_bf16_f32 v137, v140, v141
	v_cvt_pk_bf16_f32 v138, v132, v133
	v_cvt_pk_bf16_f32 v139, v134, v135
	global_store_dwordx4 v0, v[136:139], s[30:31]
	s_and_b64 vcc, exec, s[6:7]
	s_waitcnt vmcnt(15)
	v_mul_f32_e32 v152, v82, v234
	v_mul_f32_e32 v153, v83, v235
	v_mul_f32_e32 v154, v80, v232
	v_mul_f32_e32 v155, v81, v233
	s_waitcnt vmcnt(14)
	v_mul_f32_e32 v156, v78, v230
	v_mul_f32_e32 v157, v79, v231
	v_mul_f32_e32 v158, v76, v228
	v_mul_f32_e32 v159, v77, v229
	v_mul_f32_e32 v168, v74, v234
	v_mul_f32_e32 v169, v75, v235
	v_mul_f32_e32 v178, v72, v232
	v_mul_f32_e32 v179, v73, v233
	v_mul_f32_e32 v180, v70, v230
	v_mul_f32_e32 v181, v71, v231
	v_mul_f32_e32 v188, v68, v228
	v_mul_f32_e32 v189, v69, v229
	s_waitcnt vmcnt(13)
	v_fma_f32 v164, v74, v238, -v152
	v_fma_f32 v165, v75, v239, -v153
	v_fma_f32 v166, v72, v236, -v154
	v_fma_f32 v167, v73, v237, -v155
	s_waitcnt vmcnt(12)
	v_fma_f32 v160, v70, v226, -v156
	v_fma_f32 v161, v71, v227, -v157
	v_fma_f32 v162, v68, v224, -v158
	v_fma_f32 v163, v69, v225, -v159
	v_fma_f32 v156, v82, v238, v168
	v_fma_f32 v157, v83, v239, v169
	v_fma_f32 v158, v80, v236, v178
	v_fma_f32 v159, v81, v237, v179
	v_fma_f32 v152, v78, v226, v180
	v_fma_f32 v153, v79, v227, v181
	v_fma_f32 v154, v76, v224, v188
	v_fma_f32 v155, v77, v225, v189
	s_cbranch_vccnz .LBB0_702
	v_mul_f32_e32 v164, s54, v164
	v_mul_f32_e32 v165, s54, v165
	v_mul_f32_e32 v166, s54, v166
	v_mul_f32_e32 v167, s54, v167
	v_mul_f32_e32 v160, s54, v160
	v_mul_f32_e32 v161, s54, v161
	v_mul_f32_e32 v162, s54, v162
	v_mul_f32_e32 v163, s54, v163
	v_mul_f32_e32 v156, s54, v156
	v_mul_f32_e32 v157, s54, v157
	v_mul_f32_e32 v158, s54, v158
	v_mul_f32_e32 v159, s54, v159
	v_mul_f32_e32 v152, s54, v152
	v_mul_f32_e32 v153, s54, v153
	v_mul_f32_e32 v154, s54, v154
	v_mul_f32_e32 v155, s54, v155
.LBB0_702:
	v_add_u32_e32 v0, 0x30000, v3
	v_and_b32_e32 v0, -2, v0
	v_cvt_pk_bf16_f32 v166, v166, v167
	v_cvt_pk_bf16_f32 v167, v164, v165
	v_cvt_pk_bf16_f32 v168, v162, v163
	v_cvt_pk_bf16_f32 v169, v160, v161
	v_lshl_add_u64 v[160:161], s[30:31], 0, v[0:1]
	v_add_u32_e32 v0, 0x30100, v3
	global_store_dwordx4 v[160:161], v[166:169], off
	v_cvt_pk_bf16_f32 v158, v158, v159
	v_cvt_pk_bf16_f32 v159, v156, v157
	v_cvt_pk_bf16_f32 v160, v154, v155
	v_cvt_pk_bf16_f32 v161, v152, v153
	v_and_b32_e32 v0, -2, v0
	global_store_dwordx4 v0, v[158:161], s[30:31]
	v_mul_f32_e32 v152, v18, v234
	v_mul_f32_e32 v153, v19, v235
	v_mul_f32_e32 v154, v16, v232
	v_mul_f32_e32 v155, v17, v233
	v_mul_f32_e32 v156, v14, v230
	v_mul_f32_e32 v157, v15, v231
	v_mul_f32_e32 v158, v12, v228
	v_mul_f32_e32 v159, v13, v229
	v_mul_f32_e32 v142, v10, v234
	v_mul_f32_e32 v143, v11, v235
	v_mul_f32_e32 v160, v8, v232
	v_mul_f32_e32 v161, v9, v233
	v_mul_f32_e32 v138, v6, v230
	v_mul_f32_e32 v139, v7, v231
	v_mul_f32_e32 v136, v4, v228
	v_mul_f32_e32 v137, v5, v229
	v_fma_f32 v152, v10, v238, -v152
	v_fma_f32 v153, v11, v239, -v153
	v_fma_f32 v154, v8, v236, -v154
	v_fma_f32 v155, v9, v237, -v155
	v_fma_f32 v156, v6, v226, -v156
	v_fma_f32 v157, v7, v227, -v157
	v_fma_f32 v158, v4, v224, -v158
	v_fma_f32 v159, v5, v225, -v159
	v_fma_f32 v140, v18, v238, v142
	v_fma_f32 v141, v19, v239, v143
	v_fma_f32 v142, v16, v236, v160
	v_fma_f32 v143, v17, v237, v161
	v_fma_f32 v138, v14, v226, v138
	v_fma_f32 v139, v15, v227, v139
	s_and_b64 vcc, exec, s[6:7]
	v_fma_f32 v134, v12, v224, v136
	v_fma_f32 v135, v13, v225, v137
	s_cbranch_vccnz .LBB0_704
	v_mul_f32_e32 v152, s54, v152
	v_mul_f32_e32 v153, s54, v153
	v_mul_f32_e32 v154, s54, v154
	v_mul_f32_e32 v155, s54, v155
	v_mul_f32_e32 v156, s54, v156
	v_mul_f32_e32 v157, s54, v157
	v_mul_f32_e32 v158, s54, v158
	v_mul_f32_e32 v159, s54, v159
	v_mul_f32_e32 v140, s54, v140
	v_mul_f32_e32 v141, s54, v141
	v_mul_f32_e32 v142, s54, v142
	v_mul_f32_e32 v143, s54, v143
	v_mul_f32_e32 v138, s54, v138
	v_mul_f32_e32 v139, s54, v139
	v_mul_f32_e32 v134, s54, v134
	v_mul_f32_e32 v135, s54, v135

; #define PG8_GAS __attribute__((address_space(1)))
; __device__ __forceinline__ f32x4 silu4(f32x4 v) { return v * sigm4(v); }
; __device__ __forceinline__ u32x4 pack8(f32x4 v0, f32x4 v1) { u32x4 w; w.x = cvt_pk_bf16(v0[0], v0[1]); w.y = cvt_pk_bf16(v0[2], v0[3]); w.z = cvt_pk_bf16(v1[0], v1[1]); w.w = cvt_pk_bf16(v1[2], v1[3]); return w; }
;     __device__ __forceinline__ void store_rows(const f32x4& a0, const f32x4& a1, const f32x4& b0, const f32x4& b1, int type, bf16_t* base, size_t off) const {
;     ...
;         if (type == 1) { x0 = x0 * 0.0625f; x1 = x1 * 0.0625f; y0 = y0 * 0.0625f; y1 = y1 * 0.0625f; }
;         if (type == 3) { x0 = silu4(x0); x1 = silu4(x1); y0 = silu4(y0); y1 = silu4(y1); }
;         st16(base, off, pack8(x0, x1));
;         st16(base, off + HALF, pack8(y0, y1));
;     __device__ __forceinline__ void operator()(const f32x4 (&acc)[2][2][4][2], const Unit& u, int wr, int wc, int fr_in, int fq_in) const {
;     ...
;         } else if (wc < 2) {
; #pragma unroll
;             for (int ai = 0; ai < 2; ++ai) {
;                 const int pos = (4 * u.pm + 2 * ai + wr) & 63;
;                 const f32x4 c0 = *(const PG8_GAS f32x4*)(cosT + pos * 64 + fidx), c1 = *(const PG8_GAS f32x4*)(cosT + pos * 64 + fidx + 4), s0 = *(const PG8_GAS f32x4*)(sinT + pos * 64 + fidx), s1 = *(const PG8_GAS f32x4*)(sinT + pos * 64 + fidx + 4);
; #pragma unroll
;                 for (int m = 0; m < 4; ++m) { const f32x4 a0 = acc[ai][0][m][0], a1 = acc[ai][0][m][1], b0 = acc[ai][1][m][0], b1 = acc[ai][1][m][1];
;                     store_rows(a0 * c0 - b0 * s0, a1 * c1 - b1 * s1, a0 * s0 + b0 * c0, a1 * s1 + b1 * c1, type, base, (size_t)(row0 + ai * HALF + m * 16) * 2048 + coff); }
;             }
.LBB0_705:
	s_and_b64 vcc, exec, s[6:7]
	s_cbranch_vccz .LBB0_723
	s_and_b32 s6, s21, 0xfc0
	s_lshl_b32 s23, s6, 2
	s_add_u32 s6, s14, s23
	s_addc_u32 s7, s15, 0
	v_lshl_add_u64 v[136:137], s[6:7], 0, v[150:151]
	s_add_u32 s6, s12, s23
	s_addc_u32 s7, s13, 0
	v_lshl_add_u64 v[144:145], s[6:7], 0, v[150:151]
	global_load_dwordx4 v[132:135], v[136:137], off offset:16
	s_nop 0
	global_load_dwordx4 v[136:139], v[136:137], off
	s_nop 0
	global_load_dwordx4 v[140:143], v[144:145], off offset:16
	s_nop 0
	global_load_dwordx4 v[144:147], v[144:145], off
	s_add_i32 s6, s21, 0x80
	s_and_b32 s6, s6, 0xfc0
	s_lshl_b32 s6, s6, 2
	v_mov_b32_e32 v240, s6
	v_mov_b32_e32 v241, 0
	v_lshl_add_u64 v[242:243], s[14:15], 0, v[240:241]
	v_lshl_add_u64 v[242:243], v[242:243], 0, v[150:151]
	v_lshl_add_u64 v[240:241], s[12:13], 0, v[240:241]
	v_lshl_add_u64 v[240:241], v[240:241], 0, v[150:151]
	global_load_dwordx4 v[192:195], v[242:243], off offset:16
	global_load_dwordx4 v[196:199], v[242:243], off
	global_load_dwordx4 v[200:203], v[240:241], off offset:16
	global_load_dwordx4 v[204:207], v[240:241], off
	v_cndmask_b32_e64 v0, 0, 1, s[8:9]
	v_cmp_ne_u32_e64 s[6:7], 1, v0
	s_andn2_b64 vcc, exec, s[8:9]
	s_waitcnt vmcnt(4)
	v_mul_f32_e32 v152, v130, v146
	v_mul_f32_e32 v153, v131, v147
	v_mul_f32_e32 v156, v128, v144
	v_mul_f32_e32 v157, v129, v145
	v_fma_f32 v154, v122, v138, -v152
	v_fma_f32 v155, v123, v139, -v153
	v_mul_f32_e32 v152, v126, v142
	v_mul_f32_e32 v153, v127, v143
	v_mul_f32_e32 v122, v122, v146
	v_mul_f32_e32 v123, v123, v147
	v_mul_f32_e32 v160, v120, v144
	v_mul_f32_e32 v161, v121, v145
	v_fma_f32 v158, v120, v136, -v156
	v_fma_f32 v159, v121, v137, -v157
	v_mul_f32_e32 v156, v124, v140
	v_mul_f32_e32 v157, v125, v141
	v_fma_f32 v152, v118, v134, -v152
	v_fma_f32 v153, v119, v135, -v153
	v_fma_f32 v120, v130, v138, v122
	v_fma_f32 v121, v131, v139, v123
	v_fma_f32 v122, v128, v136, v160
	v_fma_f32 v123, v129, v137, v161
	v_mul_f32_e32 v118, v118, v142
	v_mul_f32_e32 v119, v119, v143
	v_mul_f32_e32 v128, v116, v140
	v_mul_f32_e32 v129, v117, v141
	v_fma_f32 v156, v116, v132, -v156
	v_fma_f32 v157, v117, v133, -v157
	v_fma_f32 v116, v126, v134, v118
	v_fma_f32 v117, v127, v135, v119
	v_fma_f32 v118, v124, v132, v128
	v_fma_f32 v119, v125, v133, v129
	s_cbranch_vccnz .LBB0_708
	v_mul_f32_e32 v154, s54, v154
	v_mul_f32_e32 v155, s54, v155
	v_mul_f32_e32 v158, s54, v158
	v_mul_f32_e32 v159, s54, v159
	v_mul_f32_e32 v152, s54, v152
	v_mul_f32_e32 v153, s54, v153
	v_mul_f32_e32 v156, s54, v156
	v_mul_f32_e32 v157, s54, v157
	v_mul_f32_e32 v120, s54, v120
	v_mul_f32_e32 v121, s54, v121
	v_mul_f32_e32 v122, s54, v122
	v_mul_f32_e32 v123, s54, v123
	v_mul_f32_e32 v116, s54, v116
	v_mul_f32_e32 v117, s54, v117
	v_mul_f32_e32 v118, s54, v118
	v_mul_f32_e32 v119, s54, v119
.LBB0_708:
	v_lshl_add_u32 v3, v2, 12, v148
	v_and_b32_e32 v0, -2, v3
	v_cvt_pk_bf16_f32 v124, v158, v159
	v_cvt_pk_bf16_f32 v125, v154, v155
	v_lshl_add_u64 v[128:129], s[30:31], 0, v[0:1]
	v_add_u32_e32 v0, 0x100, v3
	v_cvt_pk_bf16_f32 v126, v156, v157
	v_cvt_pk_bf16_f32 v127, v152, v153
	global_store_dwordx4 v[128:129], v[124:127], off
	v_cvt_pk_bf16_f32 v122, v122, v123
	v_cvt_pk_bf16_f32 v123, v120, v121
	v_and_b32_e32 v0, -2, v0
	v_mul_f32_e32 v120, v110, v142
	v_mul_f32_e32 v121, v111, v143
	v_cvt_pk_bf16_f32 v124, v118, v119
	v_cvt_pk_bf16_f32 v125, v116, v117
	v_mul_f32_e32 v116, v114, v146
	v_mul_f32_e32 v117, v115, v147
	global_store_dwordx4 v0, v[122:125], s[30:31]
	v_mul_f32_e32 v118, v112, v144
	v_mul_f32_e32 v119, v113, v145
	v_fma_f32 v116, v106, v138, -v116
	v_fma_f32 v117, v107, v139, -v117
	v_mul_f32_e32 v106, v106, v146
	v_mul_f32_e32 v107, v107, v147
	v_mul_f32_e32 v124, v104, v144
	v_mul_f32_e32 v125, v105, v145
	v_fma_f32 v118, v104, v136, -v118
	v_fma_f32 v119, v105, v137, -v119
	v_mul_f32_e32 v122, v108, v140
	v_mul_f32_e32 v123, v109, v141
	v_fma_f32 v120, v102, v134, -v120
	v_fma_f32 v121, v103, v135, -v121
	v_fma_f32 v104, v114, v138, v106
	v_fma_f32 v105, v115, v139, v107
	v_fma_f32 v106, v112, v136, v124
	v_fma_f32 v107, v113, v137, v125
	v_mul_f32_e32 v102, v102, v142
	v_mul_f32_e32 v103, v103, v143
	v_mul_f32_e32 v112, v100, v140
	v_mul_f32_e32 v113, v101, v141
	v_fma_f32 v122, v100, v132, -v122
	v_fma_f32 v123, v101, v133, -v123
	v_fma_f32 v100, v110, v134, v102
	v_fma_f32 v101, v111, v135, v103
	s_and_b64 vcc, exec, s[6:7]
	v_fma_f32 v102, v108, v132, v112
	v_fma_f32 v103, v109, v133, v113
	s_cbranch_vccnz .LBB0_710
	v_mul_f32_e32 v116, s54, v116
	v_mul_f32_e32 v117, s54, v117
	v_mul_f32_e32 v118, s54, v118
	v_mul_f32_e32 v119, s54, v119
	v_mul_f32_e32 v120, s54, v120
	v_mul_f32_e32 v121, s54, v121
	v_mul_f32_e32 v122, s54, v122
	v_mul_f32_e32 v123, s54, v123
	v_mul_f32_e32 v104, s54, v104
	v_mul_f32_e32 v105, s54, v105
	v_mul_f32_e32 v106, s54, v106
	v_mul_f32_e32 v107, s54, v107
	v_mul_f32_e32 v100, s54, v100
	v_mul_f32_e32 v101, s54, v101
	v_mul_f32_e32 v102, s54, v102
	v_mul_f32_e32 v103, s54, v103
; #define PG8_GAS __attribute__((address_space(1)))
; __device__ __forceinline__ f32x4 silu4(f32x4 v) { return v * sigm4(v); }
; __device__ __forceinline__ u32x4 pack8(f32x4 v0, f32x4 v1) { u32x4 w; w.x = cvt_pk_bf16(v0[0], v0[1]); w.y = cvt_pk_bf16(v0[2], v0[3]); w.z = cvt_pk_bf16(v1[0], v1[1]); w.w = cvt_pk_bf16(v1[2], v1[3]); return w; }
;     __device__ __forceinline__ void store_rows(const f32x4& a0, const f32x4& a1, const f32x4& b0, const f32x4& b1, int type, bf16_t* base, size_t off) const {
;     ...
;         if (type == 1) { x0 = x0 * 0.0625f; x1 = x1 * 0.0625f; y0 = y0 * 0.0625f; y1 = y1 * 0.0625f; }
;         if (type == 3) { x0 = silu4(x0); x1 = silu4(x1); y0 = silu4(y0); y1 = silu4(y1); }
;         st16(base, off, pack8(x0, x1));
;         st16(base, off + HALF, pack8(y0, y1));
;     __device__ __forceinline__ void operator()(const f32x4 (&acc)[2][2][4][2], const Unit& u, int wr, int wc, int fr_in, int fq_in) const {
;     ...
;         } else if (wc < 2) {
; #pragma unroll
;             for (int ai = 0; ai < 2; ++ai) {
;                 const int pos = (4 * u.pm + 2 * ai + wr) & 63;
;                 const f32x4 c0 = *(const PG8_GAS f32x4*)(cosT + pos * 64 + fidx), c1 = *(const PG8_GAS f32x4*)(cosT + pos * 64 + fidx + 4), s0 = *(const PG8_GAS f32x4*)(sinT + pos * 64 + fidx), s1 = *(const PG8_GAS f32x4*)(sinT + pos * 64 + fidx + 4);
; #pragma unroll
;                 for (int m = 0; m < 4; ++m) { const f32x4 a0 = acc[ai][0][m][0], a1 = acc[ai][0][m][1], b0 = acc[ai][1][m][0], b1 = acc[ai][1][m][1];
;                     store_rows(a0 * c0 - b0 * s0, a1 * c1 - b1 * s1, a0 * s0 + b0 * c0, a1 * s1 + b1 * c1, type, base, (size_t)(row0 + ai * HALF + m * 16) * 2048 + coff); }
;             }
.LBB0_710:
	v_add_u32_e32 v0, 0x10000, v3
	v_and_b32_e32 v0, -2, v0
	v_cvt_pk_bf16_f32 v108, v118, v119
	v_cvt_pk_bf16_f32 v109, v116, v117
	v_lshl_add_u64 v[112:113], s[30:31], 0, v[0:1]
	v_add_u32_e32 v0, 0x10100, v3
	v_cvt_pk_bf16_f32 v110, v122, v123
	v_cvt_pk_bf16_f32 v111, v120, v121
	global_store_dwordx4 v[112:113], v[108:111], off
	v_cvt_pk_bf16_f32 v106, v106, v107
	v_cvt_pk_bf16_f32 v107, v104, v105
	v_and_b32_e32 v0, -2, v0
	v_mul_f32_e32 v104, v94, v142
	v_mul_f32_e32 v105, v95, v143
	v_cvt_pk_bf16_f32 v108, v102, v103
	v_cvt_pk_bf16_f32 v109, v100, v101
	v_mul_f32_e32 v100, v98, v146
	v_mul_f32_e32 v101, v99, v147
	global_store_dwordx4 v0, v[106:109], s[30:31]
	v_mul_f32_e32 v102, v96, v144
	v_mul_f32_e32 v103, v97, v145
	v_fma_f32 v100, v90, v138, -v100
	v_fma_f32 v101, v91, v139, -v101
	v_mul_f32_e32 v90, v90, v146
	v_mul_f32_e32 v91, v91, v147
	v_mul_f32_e32 v108, v88, v144
	v_mul_f32_e32 v109, v89, v145
	v_fma_f32 v102, v88, v136, -v102
	v_fma_f32 v103, v89, v137, -v103
	v_mul_f32_e32 v106, v92, v140
	v_mul_f32_e32 v107, v93, v141
	v_fma_f32 v104, v86, v134, -v104
	v_fma_f32 v105, v87, v135, -v105
	v_fma_f32 v88, v98, v138, v90
	v_fma_f32 v89, v99, v139, v91
	v_fma_f32 v90, v96, v136, v108
	v_fma_f32 v91, v97, v137, v109
	v_mul_f32_e32 v86, v86, v142
	v_mul_f32_e32 v87, v87, v143
	v_mul_f32_e32 v96, v84, v140
	v_mul_f32_e32 v97, v85, v141
	v_fma_f32 v106, v84, v132, -v106
	v_fma_f32 v107, v85, v133, -v107
	v_fma_f32 v84, v94, v134, v86
	v_fma_f32 v85, v95, v135, v87
	s_and_b64 vcc, exec, s[6:7]
	v_fma_f32 v86, v92, v132, v96
	v_fma_f32 v87, v93, v133, v97
	s_cbranch_vccnz .LBB0_712
	v_mul_f32_e32 v100, s54, v100
	v_mul_f32_e32 v101, s54, v101
	v_mul_f32_e32 v102, s54, v102
	v_mul_f32_e32 v103, s54, v103
	v_mul_f32_e32 v104, s54, v104
	v_mul_f32_e32 v105, s54, v105
	v_mul_f32_e32 v106, s54, v106
	v_mul_f32_e32 v107, s54, v107
	v_mul_f32_e32 v88, s54, v88
	v_mul_f32_e32 v89, s54, v89
	v_mul_f32_e32 v90, s54, v90
	v_mul_f32_e32 v91, s54, v91
	v_mul_f32_e32 v84, s54, v84
	v_mul_f32_e32 v85, s54, v85
	v_mul_f32_e32 v86, s54, v86
	v_mul_f32_e32 v87, s54, v87
.LBB0_712:
	v_add_u32_e32 v0, 0x20000, v3
	v_and_b32_e32 v0, -2, v0
	v_cvt_pk_bf16_f32 v92, v102, v103
	v_cvt_pk_bf16_f32 v93, v100, v101
	v_lshl_add_u64 v[96:97], s[30:31], 0, v[0:1]
	v_add_u32_e32 v0, 0x20100, v3
	v_cvt_pk_bf16_f32 v94, v106, v107
	v_cvt_pk_bf16_f32 v95, v104, v105
	global_store_dwordx4 v[96:97], v[92:95], off
	v_cvt_pk_bf16_f32 v90, v90, v91
	v_cvt_pk_bf16_f32 v91, v88, v89
	v_and_b32_e32 v0, -2, v0
	v_mul_f32_e32 v88, v78, v142
	v_mul_f32_e32 v89, v79, v143
	v_cvt_pk_bf16_f32 v92, v86, v87
	v_cvt_pk_bf16_f32 v93, v84, v85
	v_mul_f32_e32 v84, v82, v146
	v_mul_f32_e32 v85, v83, v147
	global_store_dwordx4 v0, v[90:93], s[30:31]
	v_mul_f32_e32 v86, v80, v144
	v_mul_f32_e32 v87, v81, v145
	v_fma_f32 v84, v74, v138, -v84
	v_fma_f32 v85, v75, v139, -v85
	v_mul_f32_e32 v74, v74, v146
	v_mul_f32_e32 v75, v75, v147
	v_mul_f32_e32 v92, v72, v144
	v_mul_f32_e32 v93, v73, v145
	v_fma_f32 v86, v72, v136, -v86
	v_fma_f32 v87, v73, v137, -v87
	v_mul_f32_e32 v90, v76, v140
	v_mul_f32_e32 v91, v77, v141
	v_fma_f32 v88, v70, v134, -v88
	v_fma_f32 v89, v71, v135, -v89
	v_fma_f32 v72, v82, v138, v74
	v_fma_f32 v73, v83, v139, v75
	v_fma_f32 v74, v80, v136, v92
	v_fma_f32 v75, v81, v137, v93
	v_mul_f32_e32 v70, v70, v142
	v_mul_f32_e32 v71, v71, v143
	v_mul_f32_e32 v80, v68, v140
	v_mul_f32_e32 v81, v69, v141
	v_fma_f32 v90, v68, v132, -v90
	v_fma_f32 v91, v69, v133, -v91
	v_fma_f32 v68, v78, v134, v70
	v_fma_f32 v69, v79, v135, v71
	s_and_b64 vcc, exec, s[6:7]
	v_fma_f32 v70, v76, v132, v80
	v_fma_f32 v71, v77, v133, v81
	s_cbranch_vccnz .LBB0_714
	v_mul_f32_e32 v84, s54, v84
	v_mul_f32_e32 v85, s54, v85
	v_mul_f32_e32 v86, s54, v86
	v_mul_f32_e32 v87, s54, v87
	v_mul_f32_e32 v88, s54, v88
	v_mul_f32_e32 v89, s54, v89
	v_mul_f32_e32 v90, s54, v90
	v_mul_f32_e32 v91, s54, v91
	v_mul_f32_e32 v72, s54, v72
	v_mul_f32_e32 v73, s54, v73
	v_mul_f32_e32 v74, s54, v74
	v_mul_f32_e32 v75, s54, v75
	v_mul_f32_e32 v68, s54, v68
	v_mul_f32_e32 v69, s54, v69
	v_mul_f32_e32 v70, s54, v70
	v_mul_f32_e32 v71, s54, v71
.LBB0_714:
	s_addk_i32 s21, 0x80
	s_and_b32 s8, s21, 0xfc0
	v_add_u32_e32 v0, 0x30000, v3
	s_lshl_b32 s21, s8, 2
	v_and_b32_e32 v0, -2, v0
	s_add_u32 s8, s14, s21
	v_lshl_add_u64 v[80:81], s[30:31], 0, v[0:1]
	s_addc_u32 s9, s15, 0
	v_cvt_pk_bf16_f32 v76, v86, v87
	v_cvt_pk_bf16_f32 v77, v84, v85
	v_cvt_pk_bf16_f32 v78, v90, v91
	v_cvt_pk_bf16_f32 v79, v88, v89
	global_store_dwordx4 v[80:81], v[76:79], off
	v_cvt_pk_bf16_f32 v74, v74, v75
	v_cvt_pk_bf16_f32 v75, v72, v73
	v_add_u32_e32 v0, 0x30100, v3
	s_add_u32 s8, s12, s21
	v_and_b32_e32 v0, -2, v0
	s_addc_u32 s9, s13, 0
	v_cvt_pk_bf16_f32 v76, v70, v71
	v_cvt_pk_bf16_f32 v77, v68, v69
	global_store_dwordx4 v0, v[74:77], s[30:31]
	s_and_b64 vcc, exec, s[6:7]
	s_waitcnt vmcnt(8)
	v_mul_f32_e32 v84, v66, v206
	v_mul_f32_e32 v85, v67, v207
	v_mul_f32_e32 v88, v64, v204
	v_mul_f32_e32 v89, v65, v205
	v_fma_f32 v86, v58, v198, -v84
	v_fma_f32 v87, v59, v199, -v85
	v_mul_f32_e32 v84, v62, v202
	v_mul_f32_e32 v85, v63, v203
	v_mul_f32_e32 v58, v58, v206
	v_mul_f32_e32 v59, v59, v207
	v_mul_f32_e32 v92, v56, v204
	v_mul_f32_e32 v93, v57, v205
	v_fma_f32 v90, v56, v196, -v88
	v_fma_f32 v91, v57, v197, -v89
	v_mul_f32_e32 v88, v60, v200
	v_mul_f32_e32 v89, v61, v201
	v_fma_f32 v84, v54, v194, -v84
	v_fma_f32 v85, v55, v195, -v85
	v_fma_f32 v56, v66, v198, v58
	v_fma_f32 v57, v67, v199, v59
	v_fma_f32 v58, v64, v196, v92
	v_fma_f32 v59, v65, v197, v93
	v_mul_f32_e32 v54, v54, v202
	v_mul_f32_e32 v55, v55, v203
	v_mul_f32_e32 v64, v52, v200
	v_mul_f32_e32 v65, v53, v201
	v_fma_f32 v88, v52, v192, -v88
	v_fma_f32 v89, v53, v193, -v89
	v_fma_f32 v52, v62, v194, v54
	v_fma_f32 v53, v63, v195, v55
	v_fma_f32 v54, v60, v192, v64
	v_fma_f32 v55, v61, v193, v65
	s_cbranch_vccnz .LBB0_716
	v_mul_f32_e32 v86, s54, v86
	v_mul_f32_e32 v87, s54, v87
	v_mul_f32_e32 v90, s54, v90
	v_mul_f32_e32 v91, s54, v91
	v_mul_f32_e32 v84, s54, v84
	v_mul_f32_e32 v85, s54, v85
	v_mul_f32_e32 v88, s54, v88
	v_mul_f32_e32 v89, s54, v89
	v_mul_f32_e32 v56, s54, v56
	v_mul_f32_e32 v57, s54, v57
	v_mul_f32_e32 v58, s54, v58
	v_mul_f32_e32 v59, s54, v59
	v_mul_f32_e32 v52, s54, v52
	v_mul_f32_e32 v53, s54, v53
	v_mul_f32_e32 v54, s54, v54
	v_mul_f32_e32 v55, s54, v55
; #define PG8_GAS __attribute__((address_space(1)))
; __device__ __forceinline__ f32x4 silu4(f32x4 v) { return v * sigm4(v); }
; __device__ __forceinline__ u32x4 pack8(f32x4 v0, f32x4 v1) { u32x4 w; w.x = cvt_pk_bf16(v0[0], v0[1]); w.y = cvt_pk_bf16(v0[2], v0[3]); w.z = cvt_pk_bf16(v1[0], v1[1]); w.w = cvt_pk_bf16(v1[2], v1[3]); return w; }
;     __device__ __forceinline__ void store_rows(const f32x4& a0, const f32x4& a1, const f32x4& b0, const f32x4& b1, int type, bf16_t* base, size_t off) const {
;     ...
;         if (type == 1) { x0 = x0 * 0.0625f; x1 = x1 * 0.0625f; y0 = y0 * 0.0625f; y1 = y1 * 0.0625f; }
;         if (type == 3) { x0 = silu4(x0); x1 = silu4(x1); y0 = silu4(y0); y1 = silu4(y1); }
;         st16(base, off, pack8(x0, x1));
;         st16(base, off + HALF, pack8(y0, y1));
;     __device__ __forceinline__ void operator()(const f32x4 (&acc)[2][2][4][2], const Unit& u, int wr, int wc, int fr_in, int fq_in) const {
;     ...
;         } else if (wc < 2) {
; #pragma unroll
;             for (int ai = 0; ai < 2; ++ai) {
;                 const int pos = (4 * u.pm + 2 * ai + wr) & 63;
;                 const f32x4 c0 = *(const PG8_GAS f32x4*)(cosT + pos * 64 + fidx), c1 = *(const PG8_GAS f32x4*)(cosT + pos * 64 + fidx + 4), s0 = *(const PG8_GAS f32x4*)(sinT + pos * 64 + fidx), s1 = *(const PG8_GAS f32x4*)(sinT + pos * 64 + fidx + 4);
; #pragma unroll
;                 for (int m = 0; m < 4; ++m) { const f32x4 a0 = acc[ai][0][m][0], a1 = acc[ai][0][m][1], b0 = acc[ai][1][m][0], b1 = acc[ai][1][m][1];
;                     store_rows(a0 * c0 - b0 * s0, a1 * c1 - b1 * s1, a0 * s0 + b0 * c0, a1 * s1 + b1 * c1, type, base, (size_t)(row0 + ai * HALF + m * 16) * 2048 + coff); }
;             }
.LBB0_716:
	v_add_u32_e32 v0, 0x80000, v3
	v_and_b32_e32 v0, -2, v0
	v_cvt_pk_bf16_f32 v60, v90, v91
	v_cvt_pk_bf16_f32 v61, v86, v87
	v_lshl_add_u64 v[64:65], s[30:31], 0, v[0:1]
	v_add_u32_e32 v0, 0x80100, v3
	v_cvt_pk_bf16_f32 v62, v88, v89
	v_cvt_pk_bf16_f32 v63, v84, v85
	global_store_dwordx4 v[64:65], v[60:63], off
	v_cvt_pk_bf16_f32 v58, v58, v59
	v_cvt_pk_bf16_f32 v59, v56, v57
	v_and_b32_e32 v0, -2, v0
	v_mul_f32_e32 v56, v46, v202
	v_mul_f32_e32 v57, v47, v203
	v_cvt_pk_bf16_f32 v60, v54, v55
	v_cvt_pk_bf16_f32 v61, v52, v53
	v_mul_f32_e32 v52, v50, v206
	v_mul_f32_e32 v53, v51, v207
	global_store_dwordx4 v0, v[58:61], s[30:31]
	v_mul_f32_e32 v54, v48, v204
	v_mul_f32_e32 v55, v49, v205
	v_fma_f32 v52, v42, v198, -v52
	v_fma_f32 v53, v43, v199, -v53
	v_mul_f32_e32 v42, v42, v206
	v_mul_f32_e32 v43, v43, v207
	v_mul_f32_e32 v60, v40, v204
	v_mul_f32_e32 v61, v41, v205
	v_fma_f32 v54, v40, v196, -v54
	v_fma_f32 v55, v41, v197, -v55
	v_mul_f32_e32 v58, v44, v200
	v_mul_f32_e32 v59, v45, v201
	v_fma_f32 v56, v38, v194, -v56
	v_fma_f32 v57, v39, v195, -v57
	v_fma_f32 v40, v50, v198, v42
	v_fma_f32 v41, v51, v199, v43
	v_fma_f32 v42, v48, v196, v60
	v_fma_f32 v43, v49, v197, v61
	v_mul_f32_e32 v38, v38, v202
	v_mul_f32_e32 v39, v39, v203
	v_mul_f32_e32 v48, v36, v200
	v_mul_f32_e32 v49, v37, v201
	v_fma_f32 v58, v36, v192, -v58
	v_fma_f32 v59, v37, v193, -v59
	v_fma_f32 v36, v46, v194, v38
	v_fma_f32 v37, v47, v195, v39
	s_and_b64 vcc, exec, s[6:7]
	v_fma_f32 v38, v44, v192, v48
	v_fma_f32 v39, v45, v193, v49
	s_cbranch_vccnz .LBB0_718
	v_mul_f32_e32 v52, s54, v52
	v_mul_f32_e32 v53, s54, v53
	v_mul_f32_e32 v54, s54, v54
	v_mul_f32_e32 v55, s54, v55
	v_mul_f32_e32 v56, s54, v56
	v_mul_f32_e32 v57, s54, v57
	v_mul_f32_e32 v58, s54, v58
	v_mul_f32_e32 v59, s54, v59
	v_mul_f32_e32 v40, s54, v40
	v_mul_f32_e32 v41, s54, v41
	v_mul_f32_e32 v42, s54, v42
	v_mul_f32_e32 v43, s54, v43
	v_mul_f32_e32 v36, s54, v36
	v_mul_f32_e32 v37, s54, v37
	v_mul_f32_e32 v38, s54, v38
	v_mul_f32_e32 v39, s54, v39
.LBB0_718:
	v_add_u32_e32 v0, 0x90000, v3
	v_and_b32_e32 v0, -2, v0
	v_cvt_pk_bf16_f32 v44, v54, v55
	v_cvt_pk_bf16_f32 v45, v52, v53
	v_lshl_add_u64 v[48:49], s[30:31], 0, v[0:1]
	v_add_u32_e32 v0, 0x90100, v3
	v_cvt_pk_bf16_f32 v46, v58, v59
	v_cvt_pk_bf16_f32 v47, v56, v57
	global_store_dwordx4 v[48:49], v[44:47], off
	v_cvt_pk_bf16_f32 v42, v42, v43
	v_cvt_pk_bf16_f32 v43, v40, v41
	v_and_b32_e32 v0, -2, v0
	v_mul_f32_e32 v40, v30, v202
	v_mul_f32_e32 v41, v31, v203
	v_cvt_pk_bf16_f32 v44, v38, v39
	v_cvt_pk_bf16_f32 v45, v36, v37
	v_mul_f32_e32 v36, v34, v206
	v_mul_f32_e32 v37, v35, v207
	global_store_dwordx4 v0, v[42:45], s[30:31]
	v_mul_f32_e32 v38, v32, v204
	v_mul_f32_e32 v39, v33, v205
	v_fma_f32 v36, v26, v198, -v36
	v_fma_f32 v37, v27, v199, -v37
	v_mul_f32_e32 v26, v26, v206
	v_mul_f32_e32 v27, v27, v207
	v_mul_f32_e32 v44, v24, v204
	v_mul_f32_e32 v45, v25, v205
	v_fma_f32 v38, v24, v196, -v38
	v_fma_f32 v39, v25, v197, -v39
	v_mul_f32_e32 v42, v28, v200
	v_mul_f32_e32 v43, v29, v201
	v_fma_f32 v40, v22, v194, -v40
	v_fma_f32 v41, v23, v195, -v41
	v_fma_f32 v24, v34, v198, v26
	v_fma_f32 v25, v35, v199, v27
	v_fma_f32 v26, v32, v196, v44
	v_fma_f32 v27, v33, v197, v45
	v_mul_f32_e32 v22, v22, v202
	v_mul_f32_e32 v23, v23, v203
	v_mul_f32_e32 v32, v20, v200
	v_mul_f32_e32 v33, v21, v201
	v_fma_f32 v42, v20, v192, -v42
	v_fma_f32 v43, v21, v193, -v43
	v_fma_f32 v20, v30, v194, v22
	v_fma_f32 v21, v31, v195, v23
	s_and_b64 vcc, exec, s[6:7]
	v_fma_f32 v22, v28, v192, v32
	v_fma_f32 v23, v29, v193, v33
	s_cbranch_vccnz .LBB0_720
	v_mul_f32_e32 v36, s54, v36
	v_mul_f32_e32 v37, s54, v37
	v_mul_f32_e32 v38, s54, v38
	v_mul_f32_e32 v39, s54, v39
	v_mul_f32_e32 v40, s54, v40
	v_mul_f32_e32 v41, s54, v41
	v_mul_f32_e32 v42, s54, v42
	v_mul_f32_e32 v43, s54, v43
	v_mul_f32_e32 v24, s54, v24
	v_mul_f32_e32 v25, s54, v25
	v_mul_f32_e32 v26, s54, v26
	v_mul_f32_e32 v27, s54, v27
	v_mul_f32_e32 v20, s54, v20
	v_mul_f32_e32 v21, s54, v21
	v_mul_f32_e32 v22, s54, v22
	v_mul_f32_e32 v23, s54, v23
.LBB0_720:
	v_add_u32_e32 v0, 0xa0000, v3
	v_and_b32_e32 v0, -2, v0
	v_cvt_pk_bf16_f32 v28, v38, v39
	v_cvt_pk_bf16_f32 v29, v36, v37
	v_lshl_add_u64 v[32:33], s[30:31], 0, v[0:1]
	v_add_u32_e32 v0, 0xa0100, v3
	v_cvt_pk_bf16_f32 v30, v42, v43
	v_cvt_pk_bf16_f32 v31, v40, v41
	global_store_dwordx4 v[32:33], v[28:31], off
	v_cvt_pk_bf16_f32 v26, v26, v27
	v_cvt_pk_bf16_f32 v27, v24, v25
	v_and_b32_e32 v0, -2, v0
	v_mul_f32_e32 v24, v14, v202
	v_mul_f32_e32 v25, v15, v203
	v_cvt_pk_bf16_f32 v28, v22, v23
	v_cvt_pk_bf16_f32 v29, v20, v21
	v_mul_f32_e32 v20, v18, v206
	v_mul_f32_e32 v21, v19, v207
	global_store_dwordx4 v0, v[26:29], s[30:31]
	v_mul_f32_e32 v22, v16, v204
	v_mul_f32_e32 v23, v17, v205
	v_fma_f32 v20, v10, v198, -v20
	v_fma_f32 v21, v11, v199, -v21
	v_mul_f32_e32 v10, v10, v206
	v_mul_f32_e32 v11, v11, v207
	v_mul_f32_e32 v28, v8, v204
	v_mul_f32_e32 v29, v9, v205
	v_fma_f32 v22, v8, v196, -v22
	v_fma_f32 v23, v9, v197, -v23
	v_mul_f32_e32 v26, v12, v200
	v_mul_f32_e32 v27, v13, v201
	v_fma_f32 v24, v6, v194, -v24
	v_fma_f32 v25, v7, v195, -v25
	v_fma_f32 v8, v18, v198, v10
	v_fma_f32 v9, v19, v199, v11
	v_fma_f32 v10, v16, v196, v28
	v_fma_f32 v11, v17, v197, v29
	v_mul_f32_e32 v6, v6, v202
	v_mul_f32_e32 v7, v7, v203
	v_mul_f32_e32 v16, v4, v200
	v_mul_f32_e32 v17, v5, v201
	v_fma_f32 v26, v4, v192, -v26
	v_fma_f32 v27, v5, v193, -v27
	v_fma_f32 v4, v14, v194, v6
	v_fma_f32 v5, v15, v195, v7
	s_and_b64 vcc, exec, s[6:7]
	v_fma_f32 v6, v12, v192, v16
	v_fma_f32 v7, v13, v193, v17
	s_cbranch_vccnz .LBB0_722
	v_mul_f32_e32 v20, s54, v20
	v_mul_f32_e32 v21, s54, v21
	v_mul_f32_e32 v22, s54, v22
	v_mul_f32_e32 v23, s54, v23
	v_mul_f32_e32 v24, s54, v24
	v_mul_f32_e32 v25, s54, v25
	v_mul_f32_e32 v26, s54, v26
	v_mul_f32_e32 v27, s54, v27
	v_mul_f32_e32 v8, s54, v8
	v_mul_f32_e32 v9, s54, v9
	v_mul_f32_e32 v10, s54, v10
	v_mul_f32_e32 v11, s54, v11
	v_mul_f32_e32 v4, s54, v4
	v_mul_f32_e32 v5, s54, v5
	v_mul_f32_e32 v6, s54, v6
	v_mul_f32_e32 v7, s54, v7

; #define LAS __attribute__((address_space(3)))
;     ...
;             MX_BAR();
;             { const int cn = (c + PF < NCH) ? c + PF : NCH - 1; MX_LOAD(cn, u); }
;             if (MXP_SLEEP > 0) __builtin_amdgcn_s_sleep(MXP_SLEEP);
;             const int rlo = MX_ROWLO(c);
;             const bool do_out = ctx_out || c >= NCTX;
;             mx_bf16x8 aq[KS];
;             if (do_out) {
; #pragma unroll
;                 for (int ks = 0; ks < KS; ++ks) aq[ks] = frag_row(L, QS, nq0, 32 * ks, lane);
;                 for (int rep1 = 0; rep1 < MXP_S1; ++rep1) {
;                 f32x4 pt0 = ZERO4, pt1 = ZERO4;
; #pragma unroll
;                 for (int kb = 0; kb < KS; kb += 4) {
;                     mx_bf16x8 kf[2][4];
; #pragma unroll
;                     for (int ks = 0; ks < 4; ++ks) { kf[0][ks] = frag_row(L + IMG, QS, 32 * cg, 32 * (kb + ks), lane); kf[1][ks] = frag_row(L + IMG, QS, 32 * cg + 16, 32 * (kb + ks), lane); }
;                     __builtin_amdgcn_sched_barrier(0);
; #pragma unroll
;                     for (int ks = 0; ks < 4; ++ks) { pt0 = MX_MFMA(kf[0][ks], aq[kb + ks], pt0); pt1 = MX_MFMA(kf[1][ks], aq[kb + ks], pt1); }
;                     __builtin_amdgcn_sched_barrier(0);
;                 }
;                 const int m0 = 32 * cg + 4 * g, n = nq0 + i;
;                 v2u pw; pw.x = pk2((m0 <= n) ? pt0[0] : 0.f, (m0 + 1 <= n) ? pt0[1] : 0.f); pw.y = pk2((m0 + 2 <= n) ? pt0[2] : 0.f, (m0 + 3 <= n) ? pt0[3] : 0.f);
;                 *(LAS v2u*)(L + O_P + n * PS + 16 * ((m0 >> 3) ^ sw8(n)) + (m0 & 7) * 2) = pw;
;                 const int m1 = m0 + 16;
;                 pw.x = pk2((m1 <= n) ? pt1[0] : 0.f, (m1 + 1 <= n) ? pt1[1] : 0.f); pw.y = pk2((m1 + 2 <= n) ? pt1[2] : 0.f, (m1 + 3 <= n) ? pt1[3] : 0.f);
;                 *(LAS v2u*)(L + O_P + n * PS + 16 * ((m1 >> 3) ^ sw8(n)) + (m1 & 7) * 2) = pw;
;                 }
;             }
;             {
;                 mx_bf16x8 vt[4][2], ak[DT][2]; f32x4 dec[DT];
; #pragma unroll
;                 for (int te = 0; te < 4; ++te) { vt[te][0] = frag_row8(L + O_VT, 16 * te, 0, lane); vt[te][1] = frag_row8(L + O_VT, 16 * te, 32, lane); }
; #pragma unroll
;                 for (int td = 0; td < DT; ++td) { const int d0 = 16 * (DT * w + td);
;                     ak[td][0] = frag_tr(L + (HG ? 3 : 1) * IMG, QS, 0, d0, lane); ak[td][1] = frag_tr(L + (HG ? 3 : 1) * IMG, QS, 32, d0, lane);
.LBB0_798:
	s_waitcnt vmcnt(0)
	v_lshlrev_b32_e32 v6, 16, v58
	v_and_b32_e32 v7, 0xffff0000, v58
	v_mul_f32_e32 v6, v136, v6
	v_mul_f32_e32 v7, v137, v7
	v_cvt_pk_bf16_f32 v6, v6, v7
	ds_write_b16 v177, v6
	ds_write_b16_d16_hi v187, v6 offset:160
	v_lshlrev_b32_e32 v6, 16, v59
	v_and_b32_e32 v7, 0xffff0000, v59
	v_mul_f32_e32 v6, v136, v6
	v_mul_f32_e32 v7, v137, v7
	v_add_u32_e32 v34, v152, v117
	v_cvt_pk_bf16_f32 v6, v6, v7
	ds_write_b16 v177, v6 offset:320
	ds_write_b16_d16_hi v186, v6 offset:160
	v_lshlrev_b32_e32 v6, 16, v60
	v_and_b32_e32 v7, 0xffff0000, v60
	v_mul_f32_e32 v6, v136, v6
	v_mul_f32_e32 v7, v137, v7
	s_and_b64 s[24:25], s[24:25], exec
	v_cvt_pk_bf16_f32 v6, v6, v7
	ds_write_b16 v177, v6 offset:640
	ds_write_b16_d16_hi v185, v6 offset:160
	v_lshlrev_b32_e32 v6, 16, v61
	v_and_b32_e32 v7, 0xffff0000, v61
	v_mul_f32_e32 v6, v136, v6
	v_mul_f32_e32 v7, v137, v7
	v_add_u32_e32 v136, v153, v117
	v_cvt_pk_bf16_f32 v6, v6, v7
	ds_write_b16 v177, v6 offset:960
	ds_write_b16_d16_hi v184, v6 offset:160
	s_waitcnt lgkmcnt(0)
	s_barrier
	ds_read_b128 v[6:9], v34
	ds_read_b128 v[10:13], v34 offset:64
	ds_read_b128 v[14:17], v34 offset:128
	ds_read_b128 v[18:21], v34 offset:192
	ds_read_b128 v[22:25], v34 offset:256
	ds_read_b128 v[26:29], v34 offset:320
	ds_read_b128 v[30:33], v34 offset:384
	ds_read_b128 v[34:37], v34 offset:448
	ds_read_b128 v[58:61], v136 offset:34816
	ds_read_b128 v[66:69], v136 offset:34880
	ds_read_b128 v[74:77], v136 offset:43520
	ds_read_b128 v[78:81], v136 offset:43584
	ds_read_b128 v[86:89], v136 offset:34944
	ds_read_b128 v[90:93], v136 offset:35008
	ds_read_b128 v[94:97], v136 offset:43648
	ds_read_b128 v[98:101], v136 offset:43712
	s_cselect_b32 s24, 0xfc0, 0
	s_or_b32 s24, s24, s30
	s_waitcnt lgkmcnt(7)
	v_mfma_f32_16x16x32_bf16 v[58:61], v[58:61], v[6:9], v[2:5]
	s_waitcnt lgkmcnt(5)
	v_mfma_f32_16x16x32_bf16 v[74:77], v[74:77], v[6:9], v[2:5]
	v_mfma_f32_16x16x32_bf16 v[58:61], v[66:69], v[10:13], v[58:61]
	s_waitcnt lgkmcnt(4)
	v_mfma_f32_16x16x32_bf16 v[66:69], v[78:81], v[10:13], v[74:77]
	s_waitcnt lgkmcnt(3)
	v_mfma_f32_16x16x32_bf16 v[58:61], v[86:89], v[14:17], v[58:61]
	s_waitcnt lgkmcnt(1)
	v_mfma_f32_16x16x32_bf16 v[66:69], v[94:97], v[14:17], v[66:69]
	v_mfma_f32_16x16x32_bf16 v[58:61], v[90:93], v[18:21], v[58:61]
	s_waitcnt lgkmcnt(0)
	v_mfma_f32_16x16x32_bf16 v[66:69], v[98:101], v[18:21], v[66:69]
	ds_read_b128 v[74:77], v136 offset:35072
	ds_read_b128 v[78:81], v136 offset:35136
	ds_read_b128 v[86:89], v136 offset:43776
	ds_read_b128 v[90:93], v136 offset:43840
	ds_read_b128 v[94:97], v136 offset:35200
	ds_read_b128 v[98:101], v136 offset:35264
	ds_read_b128 v[102:105], v136 offset:43904
	ds_read_b128 v[136:139], v136 offset:43968
	s_waitcnt lgkmcnt(7)
	v_mfma_f32_16x16x32_bf16 v[58:61], v[74:77], v[22:25], v[58:61]
	s_waitcnt lgkmcnt(5)
	v_mfma_f32_16x16x32_bf16 v[66:69], v[86:89], v[22:25], v[66:69]
	v_mfma_f32_16x16x32_bf16 v[58:61], v[78:81], v[26:29], v[58:61]
	s_waitcnt lgkmcnt(4)
	v_mfma_f32_16x16x32_bf16 v[66:69], v[90:93], v[26:29], v[66:69]
	s_waitcnt lgkmcnt(3)
	v_mfma_f32_16x16x32_bf16 v[58:61], v[94:97], v[30:33], v[58:61]
	s_waitcnt lgkmcnt(1)
	v_mfma_f32_16x16x32_bf16 v[66:69], v[102:105], v[30:33], v[66:69]
	v_mfma_f32_16x16x32_bf16 v[58:61], v[98:101], v[34:37], v[58:61]
	s_waitcnt lgkmcnt(0)
	v_mfma_f32_16x16x32_bf16 v[66:69], v[136:139], v[34:37], v[66:69]
	s_nop 5
	v_cndmask_b32_e64 v58, v58, 0, s[8:9]
	v_cndmask_b32_e64 v59, 0, v59, s[10:11]
	v_cvt_pk_bf16_f32 v58, v58, v59
	v_cndmask_b32_e64 v59, v60, 0, s[12:13]
	v_cndmask_b32_e64 v60, v61, 0, s[14:15]
	v_cvt_pk_bf16_f32 v59, v59, v60
	v_add_u32_e32 v60, v158, v148
	ds_write_b64 v60, v[58:59]
	v_cndmask_b32_e64 v58, v66, 0, s[16:17]
	v_cndmask_b32_e64 v59, v67, 0, s[18:19]
	v_cvt_pk_bf16_f32 v58, v58, v59
	v_cndmask_b32_e64 v59, v68, 0, s[20:21]
	v_cndmask_b32_e64 v60, v69, 0, s[22:23]
	v_cvt_pk_bf16_f32 v59, v59, v60
	v_add_u32_e32 v60, v159, v148
	ds_write_b64 v60, v[58:59]
	ds_read_b128 v[58:61], v192
	ds_read_b128 v[66:69], v192 offset:64
	ds_read_b128 v[74:77], v171
	ds_read_b128 v[78:81], v171 offset:64
	ds_read_b128 v[86:89], v172
	ds_read_b128 v[90:93], v172 offset:64
	ds_read_b128 v[94:97], v173
	ds_read_b128 v[98:101], v173 offset:64
	ds_read_b64_tr_b16 v[102:103], v174 offset:34816
	ds_read_b64_tr_b16 v[104:105], v174 offset:36992
	ds_read_b64_tr_b16 v[138:139], v174 offset:37024
	ds_read_b64_tr_b16 v[136:137], v174 offset:34848
	ds_read_b64_tr_b16 v[140:141], v174 offset:52224
	ds_read_b64_tr_b16 v[142:143], v174 offset:54400
	ds_read_b64_tr_b16 v[146:147], v174 offset:54432
	ds_read_b64_tr_b16 v[144:145], v174 offset:52256
	v_mul_f32_e32 v64, v134, v64
	v_mul_f32_e32 v65, v135, v65
	v_mul_f32_e32 v62, v130, v62
	v_mul_f32_e32 v63, v131, v63
	v_mul_f32_e32 v44, v134, v44
	v_mul_f32_e32 v45, v135, v45
	v_mul_f32_e32 v42, v130, v42
	v_mul_f32_e32 v43, v131, v43
	v_mul_f32_e32 v84, v134, v84
	v_mul_f32_e32 v85, v135, v85
	v_mul_f32_e32 v82, v130, v82
	v_mul_f32_e32 v83, v131, v83
	v_mul_f32_e32 v72, v134, v72
	v_mul_f32_e32 v73, v135, v73
	v_mul_f32_e32 v70, v130, v70
	v_mul_f32_e32 v71, v131, v71
	s_waitcnt lgkmcnt(6)
	v_mfma_f32_16x16x32_bf16 v[62:65], v[102:105], v[86:89], v[62:65]
	v_mul_f32_e64 v56, v134, v56
	v_mul_f32_e64 v57, v135, v57
	v_mul_f32_e32 v54, v130, v54
	v_mul_f32_e32 v55, v131, v55
	v_mul_f32_e32 v52, v134, v52
	v_mul_f32_e32 v53, v135, v53
	v_mul_f32_e32 v50, v130, v50
	v_mul_f32_e32 v51, v131, v51
	v_mul_f32_e32 v48, v134, v48
	v_mul_f32_e32 v49, v135, v49
	v_mul_f32_e32 v46, v130, v46
	v_mul_f32_e32 v47, v131, v47
	s_waitcnt lgkmcnt(4)
	v_mfma_f32_16x16x32_bf16 v[42:45], v[136:139], v[86:89], v[42:45]
	v_mul_f32_e64 v40, v134, v40
	v_mul_f32_e64 v41, v135, v41
	v_mul_f32_e32 v38, v130, v38
	v_mul_f32_e32 v39, v131, v39
	s_waitcnt lgkmcnt(0)
	v_mfma_f32_16x16x32_bf16 v[82:85], v[102:105], v[58:61], v[82:85]
	s_barrier
;     ...
;             MX_BAR();
;             if (do_out) {
;                 if (HG) {
; #pragma unroll
;                     for (int ks = 0; ks < KS; ++ks) aq[ks] = frag_row(L + 2 * IMG, QS, nq0, 32 * ks, lane);
;                 }
;                 mx_bf16x8 vo[2][2];
;                 const mx_bf16x8 bp0 = frag_row8(L + O_P, nq0, 0, lane), bp1 = frag_row8(L + O_P, nq0, 32, lane);
; #pragma unroll
;                 for (int te = 0; te < 2; ++te) { vo[te][0] = frag_row8(L + O_VT, 32 * cg + 16 * te, 0, lane); vo[te][1] = frag_row8(L + O_VT, 32 * cg + 16 * te, 32, lane); }
;                 const int grow = rlo + (dir ? 63 - (nq0 + i) : (nq0 + i));
;                 for (int rep2 = 0; rep2 < MXP_S2; ++rep2) {
;                 f32x4 o1a = ZERO4, o1b = o1a, o2a = o1a, o2b = o1a;
; #pragma unroll
;                 for (int kb = 0; kb < KS; kb += 4) {
;                     mx_bf16x8 st[2][4];
; #pragma unroll
;                     for (int ks = 0; ks < 4; ++ks) { st[0][ks] = frag_row(L + O_ST, QS, 32 * cg, 32 * (kb + ks), lane); st[1][ks] = frag_row(L + O_ST, QS, 32 * cg + 16, 32 * (kb + ks), lane); }
;                     __builtin_amdgcn_sched_barrier(0);
;                     if (kb == 0) { o1a = MX_MFMA(vo[0][0], bp0, o1a); o1b = MX_MFMA(vo[1][0], bp0, o1b); o1a = MX_MFMA(vo[0][1], bp1, o1a); o1b = MX_MFMA(vo[1][1], bp1, o1b); }
; #pragma unroll
;                     for (int ks = 0; ks < 4; ++ks) { o2a = MX_MFMA(st[0][ks], aq[kb + ks], o2a); o2b = MX_MFMA(st[1][ks], aq[kb + ks], o2b); }
;                     __builtin_amdgcn_sched_barrier(0);
;                 }
;                 bf16* op = O + (size_t)grow * D + h * HD + eb * 64 + 32 * cg + 4 * g;
;                 if (!(VAR & 2)) { const f32x4 ya = o1a * r1 + o2a * r2, yb = o1b * r1 + o2b * r2; v2u wa, wb; wa.x = pk2(ya[0], ya[1]); wa.y = pk2(ya[2], ya[3]); wb.x = pk2(yb[0], yb[1]); wb.y = pk2(yb[2], yb[3]);
;                     *(GAS v2u*)(op) = wa; *(GAS v2u*)(op + 16) = wb; }
;                 else { asm volatile("" :: "v"(o1a), "v"(o1b), "v"(o2a), "v"(o2b)); }
;                 }
;             }
;             MX_BAR();
; #pragma unroll
;             for (int td = 0; td < DT; ++td)
; #pragma unroll
;                 for (int te = 0; te < 4; ++te) { const int d0 = 16 * (DT * w + td); const f32x4 s = accS[td][te];
;                     v2u sw; sw.x = pk2(s[0], s[1]); sw.y = pk2(s[2], s[3]);
	v_mfma_f32_16x16x32_bf16 v[70:73], v[102:105], v[74:77], v[70:73]
	v_mfma_f32_16x16x32_bf16 v[54:57], v[102:105], v[94:97], v[54:57]
	v_mfma_f32_16x16x32_bf16 v[50:53], v[136:139], v[58:61], v[50:53]
	v_mfma_f32_16x16x32_bf16 v[46:49], v[136:139], v[74:77], v[46:49]
	v_add_u32_e32 v74, v154, v117
	v_mfma_f32_16x16x32_bf16 v[38:41], v[136:139], v[94:97], v[38:41]
	v_add_u32_e32 v94, s24, v176
	v_ashrrev_i32_e32 v95, 31, v94
	v_lshlrev_b64 v[94:95], 12, v[94:95]
	s_waitcnt lgkmcnt(2)
	v_mfma_f32_16x16x32_bf16 v[62:65], v[140:143], v[90:93], v[62:65]
	v_add_u32_e32 v176, v155, v117
	s_waitcnt lgkmcnt(0)
	v_mfma_f32_16x16x32_bf16 v[42:45], v[144:147], v[90:93], v[42:45]
	v_add_u32_e32 v90, v168, v117
	v_mfma_f32_16x16x32_bf16 v[58:61], v[140:143], v[66:69], v[82:85]
	v_mfma_f32_16x16x32_bf16 v[70:73], v[140:143], v[78:81], v[70:73]
	v_mfma_f32_16x16x32_bf16 v[54:57], v[140:143], v[98:101], v[54:57]
	v_mfma_f32_16x16x32_bf16 v[50:53], v[144:147], v[66:69], v[50:53]
	ds_read_b128 v[66:69], v74
	ds_read_b128 v[74:77], v74 offset:64
	v_mfma_f32_16x16x32_bf16 v[46:49], v[144:147], v[78:81], v[46:49]
	ds_read_b128 v[78:81], v90
	ds_read_b128 v[82:85], v90 offset:64
	ds_read_b128 v[86:89], v90 offset:2560
	ds_read_b128 v[90:93], v90 offset:2624
	v_mfma_f32_16x16x32_bf16 v[38:41], v[144:147], v[98:101], v[38:41]
	v_lshl_add_u64 v[146:147], v[132:133], 0, v[94:95]
	ds_read_b128 v[94:97], v176
	ds_read_b128 v[98:101], v176 offset:8704
	ds_read_b128 v[102:105], v176 offset:64
	ds_read_b128 v[130:133], v176 offset:8768
	ds_read_b128 v[134:137], v176 offset:128
	ds_read_b128 v[138:141], v176 offset:8832
	ds_read_b128 v[142:145], v176 offset:192
	ds_read_b128 v[184:187], v176 offset:8896
	s_waitcnt lgkmcnt(11)
	v_mfma_f32_16x16x32_bf16 v[78:81], v[78:81], v[66:69], v[2:5]
	s_waitcnt lgkmcnt(9)
	v_mfma_f32_16x16x32_bf16 v[66:69], v[86:89], v[66:69], v[2:5]
	v_mfma_f32_16x16x32_bf16 v[78:81], v[82:85], v[74:77], v[78:81]
	s_waitcnt lgkmcnt(8)
	v_mfma_f32_16x16x32_bf16 v[66:69], v[90:93], v[74:77], v[66:69]
	s_waitcnt lgkmcnt(7)
	v_mfma_f32_16x16x32_bf16 v[74:77], v[94:97], v[6:9], v[2:5]
	s_waitcnt lgkmcnt(6)
	v_mfma_f32_16x16x32_bf16 v[82:85], v[98:101], v[6:9], v[2:5]
	s_waitcnt lgkmcnt(5)
	v_mfma_f32_16x16x32_bf16 v[74:77], v[102:105], v[10:13], v[74:77]
	s_waitcnt lgkmcnt(4)
	v_mfma_f32_16x16x32_bf16 v[82:85], v[130:133], v[10:13], v[82:85]
	s_waitcnt lgkmcnt(3)
	v_mfma_f32_16x16x32_bf16 v[74:77], v[134:137], v[14:17], v[74:77]
	s_waitcnt lgkmcnt(2)
	v_mfma_f32_16x16x32_bf16 v[82:85], v[138:141], v[14:17], v[82:85]
	s_waitcnt lgkmcnt(1)
	v_mfma_f32_16x16x32_bf16 v[74:77], v[142:145], v[18:21], v[74:77]
	s_waitcnt lgkmcnt(0)
	v_mfma_f32_16x16x32_bf16 v[82:85], v[184:187], v[18:21], v[82:85]
	ds_read_b128 v[86:89], v176 offset:256
	ds_read_b128 v[90:93], v176 offset:320
	ds_read_b128 v[94:97], v176 offset:8960
	ds_read_b128 v[98:101], v176 offset:9024
	ds_read_b128 v[102:105], v176 offset:384
	ds_read_b128 v[130:133], v176 offset:448
	ds_read_b128 v[134:137], v176 offset:9088
	ds_read_b128 v[138:141], v176 offset:9152
	s_waitcnt lgkmcnt(7)
	v_mfma_f32_16x16x32_bf16 v[74:77], v[86:89], v[22:25], v[74:77]
	s_waitcnt lgkmcnt(5)
	v_mfma_f32_16x16x32_bf16 v[82:85], v[94:97], v[22:25], v[82:85]
	v_mfma_f32_16x16x32_bf16 v[74:77], v[90:93], v[26:29], v[74:77]
	s_waitcnt lgkmcnt(4)
	v_mfma_f32_16x16x32_bf16 v[82:85], v[98:101], v[26:29], v[82:85]
	s_waitcnt lgkmcnt(3)
	v_mfma_f32_16x16x32_bf16 v[74:77], v[102:105], v[30:33], v[74:77]
	s_waitcnt lgkmcnt(1)
	v_mfma_f32_16x16x32_bf16 v[82:85], v[134:137], v[30:33], v[82:85]
	v_mfma_f32_16x16x32_bf16 v[74:77], v[130:133], v[34:37], v[74:77]
	s_waitcnt lgkmcnt(0)
	v_mfma_f32_16x16x32_bf16 v[82:85], v[138:141], v[34:37], v[82:85]
	s_nop 5
	v_mul_f32_e64 v76, v128, v76
	v_mul_f32_e64 v77, v129, v77
	v_mul_f32_e32 v74, v124, v74
	v_mul_f32_e32 v75, v125, v75
	v_fma_f32 v76, v126, v80, v76
	v_fma_f32 v77, v127, v81, v77
	v_fma_f32 v74, v122, v78, v74
	v_fma_f32 v75, v123, v79, v75
	v_mul_f32_e32 v78, v128, v84
	v_mul_f32_e32 v79, v129, v85
	v_mul_f32_e32 v80, v124, v82
	v_mul_f32_e32 v81, v125, v83
	v_fma_f32 v68, v126, v68, v78
	v_fma_f32 v69, v127, v69, v79
	v_fma_f32 v66, v122, v66, v80
	v_fma_f32 v67, v123, v67, v81
	v_cvt_pk_bf16_f32 v74, v74, v75
	v_cvt_pk_bf16_f32 v75, v76, v77
	v_cvt_pk_bf16_f32 v66, v66, v67
	v_cvt_pk_bf16_f32 v67, v68, v69
	global_store_dwordx2 v[146:147], v[74:75], off
	global_store_dwordx2 v[146:147], v[66:67], off offset:32
	s_waitcnt lgkmcnt(0)
	s_barrier
	s_add_i32 s44, s44, s3
	v_cvt_pk_bf16_f32 v58, v58, v59
	v_cvt_pk_bf16_f32 v59, v60, v61
	v_cvt_pk_bf16_f32 v60, v70, v71
	v_cvt_pk_bf16_f32 v61, v72, v73
	v_cvt_pk_bf16_f32 v62, v62, v63
	v_cvt_pk_bf16_f32 v63, v64, v65
	v_cvt_pk_bf16_f32 v54, v54, v55
	v_cvt_pk_bf16_f32 v55, v56, v57
	v_cvt_pk_bf16_f32 v50, v50, v51
	v_cvt_pk_bf16_f32 v51, v52, v53
	v_cvt_pk_bf16_f32 v46, v46, v47
	v_cvt_pk_bf16_f32 v47, v48, v49
	v_cvt_pk_bf16_f32 v42, v42, v43
	v_cvt_pk_bf16_f32 v43, v44, v45
	v_cvt_pk_bf16_f32 v38, v38, v39
	v_cvt_pk_bf16_f32 v39, v40, v41
	s_cmpk_gt_i32 s44, 0xff
	ds_write2_b64 v175, v[58:59], v[50:51] offset1:4
	ds_write2_b64 v193, v[60:61], v[46:47] offset0:64 offset1:68
	ds_write2_b64 v194, v[62:63], v[42:43] offset0:128 offset1:132
	ds_write2_b64 v195, v[54:55], v[38:39] offset0:192 offset1:196
	s_cbranch_scc1 .LBB0_809

; #define LAS __attribute__((address_space(3)))
; __device__ __forceinline__ unsigned pk2(float lo, float hi) { const f32x2_t v = {lo, hi}; const bf16x2_t b = __builtin_convertvector(v, bf16x2_t); return __builtin_bit_cast(unsigned, b); }
; #define MX_MFMA(a, b, c) __builtin_amdgcn_mfma_f32_16x16x32_bf16((a), (b), (c), 0, 0, 0)
; #define MX_BAR() do { asm volatile("s_waitcnt lgkmcnt(0)" ::: "memory"); __builtin_amdgcn_s_barrier(); if (MXP_BAR > 1) __builtin_amdgcn_s_barrier(); asm volatile("" ::: "memory"); } while (0)
;     ...
;             MX_BAR();
;             { const int cn = (c + PF < NCH) ? c + PF : NCH - 1; MX_LOAD(cn, u); }
;             if (MXP_SLEEP > 0) __builtin_amdgcn_s_sleep(MXP_SLEEP);
;             const int rlo = MX_ROWLO(c);
;             const bool do_out = ctx_out || c >= NCTX;
;             mx_bf16x8 aq[KS];
;             if (do_out) {
; #pragma unroll
;                 for (int ks = 0; ks < KS; ++ks) aq[ks] = frag_row(L, QS, nq0, 32 * ks, lane);
;                 for (int rep1 = 0; rep1 < MXP_S1; ++rep1) {
;                 f32x4 pt0 = ZERO4, pt1 = ZERO4;
; #pragma unroll
;                 for (int kb = 0; kb < KS; kb += 4) {
;                     mx_bf16x8 kf[2][4];
; #pragma unroll
;                     for (int ks = 0; ks < 4; ++ks) { kf[0][ks] = frag_row(L + IMG, QS, 32 * cg, 32 * (kb + ks), lane); kf[1][ks] = frag_row(L + IMG, QS, 32 * cg + 16, 32 * (kb + ks), lane); }
;                     __builtin_amdgcn_sched_barrier(0);
; #pragma unroll
;                     for (int ks = 0; ks < 4; ++ks) { pt0 = MX_MFMA(kf[0][ks], aq[kb + ks], pt0); pt1 = MX_MFMA(kf[1][ks], aq[kb + ks], pt1); }
;                     __builtin_amdgcn_sched_barrier(0);
;                 }
;                 const int m0 = 32 * cg + 4 * g, n = nq0 + i;
;                 v2u pw; pw.x = pk2((m0 <= n) ? pt0[0] : 0.f, (m0 + 1 <= n) ? pt0[1] : 0.f); pw.y = pk2((m0 + 2 <= n) ? pt0[2] : 0.f, (m0 + 3 <= n) ? pt0[3] : 0.f);
;                 *(LAS v2u*)(L + O_P + n * PS + 16 * ((m0 >> 3) ^ sw8(n)) + (m0 & 7) * 2) = pw;
;                 const int m1 = m0 + 16;
;                 pw.x = pk2((m1 <= n) ? pt1[0] : 0.f, (m1 + 1 <= n) ? pt1[1] : 0.f); pw.y = pk2((m1 + 2 <= n) ? pt1[2] : 0.f, (m1 + 3 <= n) ? pt1[3] : 0.f);
;                 *(LAS v2u*)(L + O_P + n * PS + 16 * ((m1 >> 3) ^ sw8(n)) + (m1 & 7) * 2) = pw;
.LBB0_803:
	s_add_i32 s31, s27, 1
	s_add_i32 s34, s35, -1
	v_sub_co_u32_e64 v178, s[36:37], s27, 3
	s_and_b64 s[28:29], s[24:25], exec
	s_waitcnt vmcnt(0)
	v_lshlrev_b32_e32 v66, 16, v58
	v_and_b32_e32 v67, 0xffff0000, v58
	v_readfirstlane_b32 s28, v178
	v_mul_f32_e32 v66, v136, v66
	v_mul_f32_e32 v67, v137, v67
	s_cselect_b32 s28, s28, s34
	v_cvt_pk_bf16_f32 v58, v66, v67
	s_lshl_b32 s40, s28, 6
	s_add_i32 s41, s35, 0xffffffbf
	ds_write_b16 v177, v58
	ds_write_b16_d16_hi v187, v58 offset:160
	v_lshlrev_b32_e32 v58, 16, v59
	v_and_b32_e32 v59, 0xffff0000, v59
	s_and_b64 s[28:29], s[24:25], exec
	v_mul_f32_e32 v58, v136, v58
	v_mul_f32_e32 v59, v137, v59
	s_cselect_b32 s28, s31, s41
	v_cvt_pk_bf16_f32 v58, v58, v59
	s_lshl_b32 s28, s28, 6
	ds_write_b16 v177, v58 offset:320
	ds_write_b16_d16_hi v186, v58 offset:160
	v_lshlrev_b32_e32 v58, 16, v60
	v_and_b32_e32 v59, 0xffff0000, v60
	s_add_i32 s41, s28, s26
	v_mul_f32_e32 v58, v136, v58
	v_mul_f32_e32 v59, v137, v59
	s_cmp_gt_u32 s27, 3
	v_cvt_pk_bf16_f32 v58, v58, v59
	s_cselect_b64 s[28:29], -1, 0
	ds_write_b16 v177, v58 offset:640
	ds_write_b16_d16_hi v185, v58 offset:160
	v_lshlrev_b32_e32 v58, 16, v61
	v_and_b32_e32 v59, 0xffff0000, v61
	s_add_i32 s40, s40, s30
	v_mul_f32_e32 v58, v136, v58
	v_mul_f32_e32 v59, v137, v59
	s_and_b64 s[36:37], s[36:37], exec
	v_cvt_pk_bf16_f32 v58, v58, v59
	s_cselect_b32 s36, s41, s40
	ds_write_b16 v177, v58 offset:960
	ds_write_b16_d16_hi v184, v58 offset:160
	v_add_u32_e32 v58, s36, v149
	v_ashrrev_i32_e32 v59, 31, v58
	v_lshlrev_b64 v[58:59], 11, v[58:59]
	v_lshl_add_u64 v[58:59], v[58:59], 0, v[138:139]
	v_lshlrev_b64 v[58:59], 1, v[58:59]
	s_waitcnt lgkmcnt(0)
	s_barrier
	v_lshl_add_u64 v[60:61], v[106:107], 0, v[58:59]
	v_lshl_add_u64 v[58:59], v[108:109], 0, v[58:59]
	global_load_dwordx4 v[66:69], v[60:61], off
	global_load_dwordx4 v[74:77], v[58:59], off
	v_add_u32_e32 v58, s36, v156
	v_ashrrev_i32_e32 v59, 31, v58
	v_lshlrev_b64 v[58:59], 11, v[58:59]
	v_lshl_add_u64 v[58:59], v[58:59], 0, v[140:141]
	v_lshlrev_b64 v[58:59], 1, v[58:59]
	v_lshl_add_u64 v[60:61], v[106:107], 0, v[58:59]
	v_lshl_add_u64 v[58:59], v[108:109], 0, v[58:59]
	global_load_dwordx4 v[78:81], v[60:61], off
	global_load_dwordx4 v[86:89], v[58:59], off
	v_add_u32_e32 v58, s36, v161
	v_ashrrev_i32_e32 v59, 31, v58
	v_lshlrev_b64 v[58:59], 11, v[58:59]
	v_lshl_add_u64 v[58:59], v[58:59], 0, v[142:143]
	v_lshlrev_b64 v[58:59], 1, v[58:59]
	v_lshl_add_u64 v[60:61], v[106:107], 0, v[58:59]
	v_lshl_add_u64 v[58:59], v[108:109], 0, v[58:59]
	global_load_dwordx4 v[90:93], v[60:61], off
	global_load_dwordx4 v[94:97], v[58:59], off
	v_add_u32_e32 v58, s36, v163
	v_ashrrev_i32_e32 v59, 31, v58
	v_lshlrev_b64 v[58:59], 11, v[58:59]
	v_lshl_add_u64 v[58:59], v[58:59], 0, v[144:145]
	v_lshlrev_b64 v[58:59], 1, v[58:59]
	v_lshl_add_u64 v[60:61], v[106:107], 0, v[58:59]
	v_lshl_add_u64 v[58:59], v[108:109], 0, v[58:59]
	global_load_dwordx4 v[98:101], v[60:61], off
	global_load_dwordx4 v[102:105], v[58:59], off
	v_or_b32_e32 v58, s36, v113
	v_ashrrev_i32_e32 v59, 31, v58
	v_lshlrev_b64 v[58:59], 12, v[58:59]
	v_lshl_add_u64 v[58:59], v[146:147], 0, v[58:59]
	global_load_dwordx4 v[58:61], v[58:59], off
	s_or_b64 s[28:29], s[4:5], s[28:29]
	s_and_b64 vcc, exec, s[28:29]
	s_cbranch_vccz .LBB0_805
	v_add_u32_e32 v34, v152, v117
	v_add_u32_e32 v178, v153, v117
	ds_read_b128 v[6:9], v34
	ds_read_b128 v[10:13], v34 offset:64
	ds_read_b128 v[14:17], v34 offset:128
	ds_read_b128 v[18:21], v34 offset:192
	ds_read_b128 v[22:25], v34 offset:256
	ds_read_b128 v[26:29], v34 offset:320
	ds_read_b128 v[30:33], v34 offset:384
	ds_read_b128 v[34:37], v34 offset:448
	ds_read_b128 v[192:195], v178 offset:34816
	ds_read_b128 v[196:199], v178 offset:34880
	ds_read_b128 v[200:203], v178 offset:43520
	ds_read_b128 v[204:207], v178 offset:43584
	ds_read_b128 v[208:211], v178 offset:34944
	ds_read_b128 v[212:215], v178 offset:35008
	ds_read_b128 v[216:219], v178 offset:43648
	ds_read_b128 v[228:231], v178 offset:43712
	s_waitcnt lgkmcnt(7)
	v_mfma_f32_16x16x32_bf16 v[192:195], v[192:195], v[6:9], v[2:5]
	s_waitcnt lgkmcnt(5)
	v_mfma_f32_16x16x32_bf16 v[200:203], v[200:203], v[6:9], v[2:5]
	v_mfma_f32_16x16x32_bf16 v[192:195], v[196:199], v[10:13], v[192:195]
	s_waitcnt lgkmcnt(4)
	v_mfma_f32_16x16x32_bf16 v[196:199], v[204:207], v[10:13], v[200:203]
	s_waitcnt lgkmcnt(3)
	v_mfma_f32_16x16x32_bf16 v[192:195], v[208:211], v[14:17], v[192:195]
	s_waitcnt lgkmcnt(1)
	v_mfma_f32_16x16x32_bf16 v[196:199], v[216:219], v[14:17], v[196:199]
	v_mfma_f32_16x16x32_bf16 v[192:195], v[212:215], v[18:21], v[192:195]
	s_waitcnt lgkmcnt(0)
	v_mfma_f32_16x16x32_bf16 v[196:199], v[228:231], v[18:21], v[196:199]
	ds_read_b128 v[200:203], v178 offset:35072
	ds_read_b128 v[204:207], v178 offset:35136
	ds_read_b128 v[208:211], v178 offset:43776
	ds_read_b128 v[212:215], v178 offset:43840
	ds_read_b128 v[216:219], v178 offset:35200
	ds_read_b128 v[228:231], v178 offset:35264
	ds_read_b128 v[232:235], v178 offset:43904
	ds_read_b128 v[236:239], v178 offset:43968
	s_waitcnt lgkmcnt(7)
	v_mfma_f32_16x16x32_bf16 v[192:195], v[200:203], v[22:25], v[192:195]
	s_waitcnt lgkmcnt(5)
	v_mfma_f32_16x16x32_bf16 v[196:199], v[208:211], v[22:25], v[196:199]
	v_mfma_f32_16x16x32_bf16 v[192:195], v[204:207], v[26:29], v[192:195]
	s_waitcnt lgkmcnt(4)
	v_mfma_f32_16x16x32_bf16 v[196:199], v[212:215], v[26:29], v[196:199]
	s_waitcnt lgkmcnt(3)
	v_mfma_f32_16x16x32_bf16 v[192:195], v[216:219], v[30:33], v[192:195]
	s_waitcnt lgkmcnt(1)
	v_mfma_f32_16x16x32_bf16 v[196:199], v[232:235], v[30:33], v[196:199]
	v_mfma_f32_16x16x32_bf16 v[192:195], v[228:231], v[34:37], v[192:195]
	s_waitcnt lgkmcnt(0)
	v_mfma_f32_16x16x32_bf16 v[196:199], v[236:239], v[34:37], v[196:199]
	s_nop 5
	v_cndmask_b32_e64 v178, v192, 0, s[8:9]
	v_cndmask_b32_e64 v179, 0, v193, s[10:11]
	v_cvt_pk_bf16_f32 v178, v178, v179
	v_cndmask_b32_e64 v179, v194, 0, s[12:13]
	v_cndmask_b32_e64 v180, v195, 0, s[14:15]
	v_cvt_pk_bf16_f32 v179, v179, v180
	v_add_u32_e32 v180, v158, v148
	ds_write_b64 v180, v[178:179]
	v_cndmask_b32_e64 v178, v196, 0, s[16:17]
	v_cndmask_b32_e64 v179, v197, 0, s[18:19]
	v_cvt_pk_bf16_f32 v178, v178, v179
	v_cndmask_b32_e64 v179, v198, 0, s[20:21]
	v_cndmask_b32_e64 v180, v199, 0, s[22:23]
	v_cvt_pk_bf16_f32 v179, v179, v180
	v_add_u32_e32 v180, v159, v148
	ds_write_b64 v180, v[178:179]
; #define LAS __attribute__((address_space(3)))
; #define MX_MFMA(a, b, c) __builtin_amdgcn_mfma_f32_16x16x32_bf16((a), (b), (c), 0, 0, 0)
;     ...
;             {
;                 mx_bf16x8 vt[4][2], ak[DT][2]; f32x4 dec[DT];
; #pragma unroll
;                 for (int te = 0; te < 4; ++te) { vt[te][0] = frag_row8(L + O_VT, 16 * te, 0, lane); vt[te][1] = frag_row8(L + O_VT, 16 * te, 32, lane); }
; #pragma unroll
;                 for (int td = 0; td < DT; ++td) { const int d0 = 16 * (DT * w + td);
;                     ak[td][0] = frag_tr(L + (HG ? 3 : 1) * IMG, QS, 0, d0, lane); ak[td][1] = frag_tr(L + (HG ? 3 : 1) * IMG, QS, 32, d0, lane);
;                     dec[td] = (f32x4){cdec, cdec, cdec, cdec};
;                     if (HG) { const f32x4 ce = *(const LAS f32x4*)(L + O_TOT + 2048 + (d0 + 4 * g) * 4); dec[td] = (f32x4){__expf(ce[0]), __expf(ce[1]), __expf(ce[2]), __expf(ce[3])}; } }
;                 __builtin_amdgcn_sched_barrier(0);
; #pragma unroll
;                 for (int td = 0; td < DT; ++td)
; #pragma unroll
;                     for (int te = 0; te < 4; ++te) accS[td][te] = MX_MFMA(ak[td][0], vt[te][0], accS[td][te] * dec[td]);
.LBB0_805:
	v_add_u32_e32 v192, v167, v117
	ds_read_b128 v[194:197], v192
	ds_read_b128 v[198:201], v192 offset:64
	ds_read_b128 v[202:205], v171
	ds_read_b128 v[206:209], v171 offset:64
	ds_read_b128 v[210:213], v172
	ds_read_b128 v[214:217], v172 offset:64
	ds_read_b128 v[228:231], v173
	ds_read_b128 v[232:235], v173 offset:64
	ds_read_b64_tr_b16 v[236:237], v174 offset:34816
	ds_read_b64_tr_b16 v[238:239], v174 offset:36992
	ds_read_b64_tr_b16 v[242:243], v174 offset:37024
	ds_read_b64_tr_b16 v[240:241], v174 offset:34848
	ds_read_b64_tr_b16 v[244:245], v174 offset:52224
	ds_read_b64_tr_b16 v[246:247], v174 offset:54400
	ds_read_b64_tr_b16 v[250:251], v174 offset:54432
	ds_read_b64_tr_b16 v[248:249], v174 offset:52256
	v_mul_f32_e32 v84, v134, v84
	v_mul_f32_e32 v85, v135, v85
	v_mul_f32_e32 v82, v130, v82
	v_mul_f32_e32 v83, v131, v83
	v_mul_f32_e32 v72, v134, v72
	v_mul_f32_e32 v73, v135, v73
	v_mul_f32_e32 v70, v130, v70
	v_mul_f32_e32 v71, v131, v71
	v_mul_f32_e32 v64, v134, v64
	v_mul_f32_e32 v65, v135, v65
	v_mul_f32_e32 v62, v130, v62
	v_mul_f32_e32 v63, v131, v63
	v_mul_f32_e32 v56, v134, v56
	v_mul_f32_e32 v57, v135, v57
	v_mul_f32_e32 v54, v130, v54
	v_mul_f32_e32 v55, v131, v55
	v_mul_f32_e32 v52, v134, v52
	v_mul_f32_e32 v53, v135, v53
	v_mul_f32_e32 v50, v130, v50
	v_mul_f32_e32 v51, v131, v51
	v_mul_f32_e32 v48, v134, v48
	v_mul_f32_e32 v49, v135, v49
	v_mul_f32_e32 v46, v130, v46
	v_mul_f32_e32 v47, v131, v47
	v_mul_f32_e32 v44, v134, v44
	v_mul_f32_e32 v45, v135, v45
	v_mul_f32_e32 v42, v130, v42
	v_mul_f32_e32 v43, v131, v43
	v_mul_f32_e32 v40, v134, v40
	v_mul_f32_e32 v41, v135, v41
	v_mul_f32_e32 v38, v130, v38
	v_mul_f32_e32 v39, v131, v39
	s_waitcnt lgkmcnt(6)
	v_mfma_f32_16x16x32_bf16 v[82:85], v[236:239], v[194:197], v[82:85]
	s_waitcnt lgkmcnt(0)
	s_barrier
	v_mfma_f32_16x16x32_bf16 v[70:73], v[236:239], v[202:205], v[70:73]
	s_andn2_b64 vcc, exec, s[28:29]
	v_mfma_f32_16x16x32_bf16 v[62:65], v[236:239], v[210:213], v[62:65]
	v_mfma_f32_16x16x32_bf16 v[54:57], v[236:239], v[228:231], v[54:57]
	s_waitcnt lgkmcnt(4)
	v_mfma_f32_16x16x32_bf16 v[50:53], v[240:243], v[194:197], v[50:53]
	v_mfma_f32_16x16x32_bf16 v[46:49], v[240:243], v[202:205], v[46:49]
	v_mfma_f32_16x16x32_bf16 v[42:45], v[240:243], v[210:213], v[42:45]
	v_mfma_f32_16x16x32_bf16 v[38:41], v[240:243], v[228:231], v[38:41]
	s_waitcnt lgkmcnt(2)
	v_mfma_f32_16x16x32_bf16 v[82:85], v[244:247], v[198:201], v[82:85]
	v_mfma_f32_16x16x32_bf16 v[70:73], v[244:247], v[206:209], v[70:73]
	v_mfma_f32_16x16x32_bf16 v[62:65], v[244:247], v[214:217], v[62:65]
	v_mfma_f32_16x16x32_bf16 v[54:57], v[244:247], v[232:235], v[54:57]
	s_waitcnt lgkmcnt(0)
	v_mfma_f32_16x16x32_bf16 v[50:53], v[248:251], v[198:201], v[50:53]
	v_mfma_f32_16x16x32_bf16 v[46:49], v[248:251], v[206:209], v[46:49]
	v_mfma_f32_16x16x32_bf16 v[42:45], v[248:251], v[214:217], v[42:45]
	v_mfma_f32_16x16x32_bf16 v[38:41], v[248:251], v[232:235], v[38:41]
	s_cbranch_vccnz ret_stage_skip
; #define GAS __attribute__((address_space(1)))
; __device__ __forceinline__ unsigned pk2(float lo, float hi) { const f32x2_t v = {lo, hi}; const bf16x2_t b = __builtin_convertvector(v, bf16x2_t); return __builtin_bit_cast(unsigned, b); }
; #define MX_MFMA(a, b, c) __builtin_amdgcn_mfma_f32_16x16x32_bf16((a), (b), (c), 0, 0, 0)
;     ...
;             if (do_out) {
;                 if (HG) {
; #pragma unroll
;                     for (int ks = 0; ks < KS; ++ks) aq[ks] = frag_row(L + 2 * IMG, QS, nq0, 32 * ks, lane);
;                 }
;                 mx_bf16x8 vo[2][2];
;                 const mx_bf16x8 bp0 = frag_row8(L + O_P, nq0, 0, lane), bp1 = frag_row8(L + O_P, nq0, 32, lane);
; #pragma unroll
;                 for (int te = 0; te < 2; ++te) { vo[te][0] = frag_row8(L + O_VT, 32 * cg + 16 * te, 0, lane); vo[te][1] = frag_row8(L + O_VT, 32 * cg + 16 * te, 32, lane); }
;                 const int grow = rlo + (dir ? 63 - (nq0 + i) : (nq0 + i));
;                 for (int rep2 = 0; rep2 < MXP_S2; ++rep2) {
;                 f32x4 o1a = ZERO4, o1b = o1a, o2a = o1a, o2b = o1a;
; #pragma unroll
;                 for (int kb = 0; kb < KS; kb += 4) {
;                     mx_bf16x8 st[2][4];
; #pragma unroll
;                     for (int ks = 0; ks < 4; ++ks) { st[0][ks] = frag_row(L + O_ST, QS, 32 * cg, 32 * (kb + ks), lane); st[1][ks] = frag_row(L + O_ST, QS, 32 * cg + 16, 32 * (kb + ks), lane); }
;                     __builtin_amdgcn_sched_barrier(0);
;                     if (kb == 0) { o1a = MX_MFMA(vo[0][0], bp0, o1a); o1b = MX_MFMA(vo[1][0], bp0, o1b); o1a = MX_MFMA(vo[0][1], bp1, o1a); o1b = MX_MFMA(vo[1][1], bp1, o1b); }
; #pragma unroll
;                     for (int ks = 0; ks < 4; ++ks) { o2a = MX_MFMA(st[0][ks], aq[kb + ks], o2a); o2b = MX_MFMA(st[1][ks], aq[kb + ks], o2b); }
;                     __builtin_amdgcn_sched_barrier(0);
;                 }
;                 bf16* op = O + (size_t)grow * D + h * HD + eb * 64 + 32 * cg + 4 * g;
;                 if (!(VAR & 2)) { const f32x4 ya = o1a * r1 + o2a * r2, yb = o1b * r1 + o2b * r2; v2u wa, wb; wa.x = pk2(ya[0], ya[1]); wa.y = pk2(ya[2], ya[3]); wb.x = pk2(yb[0], yb[1]); wb.y = pk2(yb[2], yb[3]);
;                     *(GAS v2u*)(op) = wa; *(GAS v2u*)(op + 16) = wb; }
;                 else { asm volatile("" :: "v"(o1a), "v"(o1b), "v"(o2a), "v"(o2b)); }
	v_sub_co_u32_e64 v178, s[28:29], s27, 4
	s_and_b64 s[36:37], s[24:25], exec
	v_readfirstlane_b32 s36, v178
	s_cselect_b32 s36, s36, s35
	s_lshl_b32 s40, s36, 6
	s_sub_i32 s35, s35, 64
	s_and_b64 s[36:37], s[24:25], exec
	s_cselect_b32 s27, s27, s35
	s_lshl_b32 s27, s27, 6
	s_add_i32 s27, s27, s26
	s_add_i32 s40, s40, s30
	s_and_b64 s[28:29], s[28:29], exec
	v_add_u32_e32 v178, v154, v117
	s_cselect_b32 s27, s27, s40
	ds_read_b128 v[194:197], v178
	ds_read_b128 v[198:201], v178 offset:64
	v_add_u32_e32 v178, v168, v117
	ds_read_b128 v[202:205], v178
	ds_read_b128 v[206:209], v178 offset:64
	ds_read_b128 v[210:213], v178 offset:2560
	ds_read_b128 v[214:217], v178 offset:2624
	v_add_u32_e32 v178, s27, v176
	v_ashrrev_i32_e32 v179, 31, v178
	v_lshlrev_b64 v[178:179], 12, v[178:179]
	v_add_u32_e32 v193, v155, v117
	v_lshl_add_u64 v[218:219], v[132:133], 0, v[178:179]
	ds_read_b128 v[228:231], v193
	ds_read_b128 v[232:235], v193 offset:8704
	ds_read_b128 v[236:239], v193 offset:64
	ds_read_b128 v[240:243], v193 offset:8768
	ds_read_b128 v[244:247], v193 offset:128
	ds_read_b128 v[248:251], v193 offset:8832
	ds_read_b128 v[178:181], v193 offset:192
	ds_read_b128 v[224:227], v193 offset:8896
	s_waitcnt lgkmcnt(11)
	v_mfma_f32_16x16x32_bf16 v[202:205], v[202:205], v[194:197], v[2:5]
	s_waitcnt lgkmcnt(9)
	v_mfma_f32_16x16x32_bf16 v[194:197], v[210:213], v[194:197], v[2:5]
	v_mfma_f32_16x16x32_bf16 v[202:205], v[206:209], v[198:201], v[202:205]
	s_waitcnt lgkmcnt(8)
	v_mfma_f32_16x16x32_bf16 v[194:197], v[214:217], v[198:201], v[194:197]
	s_waitcnt lgkmcnt(7)
	v_mfma_f32_16x16x32_bf16 v[198:201], v[228:231], v[6:9], v[2:5]
	s_waitcnt lgkmcnt(6)
	v_mfma_f32_16x16x32_bf16 v[206:209], v[232:235], v[6:9], v[2:5]
	s_waitcnt lgkmcnt(5)
	v_mfma_f32_16x16x32_bf16 v[198:201], v[236:239], v[10:13], v[198:201]
	s_waitcnt lgkmcnt(4)
	v_mfma_f32_16x16x32_bf16 v[206:209], v[240:243], v[10:13], v[206:209]
	s_waitcnt lgkmcnt(3)
	v_mfma_f32_16x16x32_bf16 v[198:201], v[244:247], v[14:17], v[198:201]
	s_waitcnt lgkmcnt(2)
	v_mfma_f32_16x16x32_bf16 v[206:209], v[248:251], v[14:17], v[206:209]
	s_waitcnt lgkmcnt(1)
	v_mfma_f32_16x16x32_bf16 v[178:181], v[178:181], v[18:21], v[198:201]
	s_waitcnt lgkmcnt(0)
	v_mfma_f32_16x16x32_bf16 v[198:201], v[224:227], v[18:21], v[206:209]
	s_nop 3
	ds_read_b128 v[206:209], v193 offset:256
	ds_read_b128 v[210:213], v193 offset:320
	ds_read_b128 v[214:217], v193 offset:8960
	ds_read_b128 v[224:227], v193 offset:9024
	ds_read_b128 v[228:231], v193 offset:384
	ds_read_b128 v[232:235], v193 offset:448
	ds_read_b128 v[236:239], v193 offset:9088
	ds_read_b128 v[240:243], v193 offset:9152
	s_waitcnt lgkmcnt(7)
	v_mfma_f32_16x16x32_bf16 v[178:181], v[206:209], v[22:25], v[178:181]
	s_waitcnt lgkmcnt(5)
	v_mfma_f32_16x16x32_bf16 v[198:201], v[214:217], v[22:25], v[198:201]
	v_mfma_f32_16x16x32_bf16 v[178:181], v[210:213], v[26:29], v[178:181]
	s_waitcnt lgkmcnt(4)
	v_mfma_f32_16x16x32_bf16 v[198:201], v[224:227], v[26:29], v[198:201]
	s_waitcnt lgkmcnt(3)
	v_mfma_f32_16x16x32_bf16 v[178:181], v[228:231], v[30:33], v[178:181]
	s_waitcnt lgkmcnt(1)
	v_mfma_f32_16x16x32_bf16 v[198:201], v[236:239], v[30:33], v[198:201]
	v_mfma_f32_16x16x32_bf16 v[178:181], v[232:235], v[34:37], v[178:181]
	s_waitcnt lgkmcnt(0)
	v_mfma_f32_16x16x32_bf16 v[198:201], v[240:243], v[34:37], v[198:201]
	s_waitcnt vmcnt(8)
	ds_write_b128 v191, v[66:69]
	s_waitcnt vmcnt(7)
	ds_write_b128 v191, v[74:77] offset:34816
	s_waitcnt vmcnt(6)
	ds_write_b128 v190, v[78:81]
	s_waitcnt vmcnt(5)
	ds_write_b128 v190, v[86:89] offset:34816
	s_waitcnt vmcnt(4)
	ds_write_b128 v189, v[90:93]
	s_waitcnt vmcnt(3)
	ds_write_b128 v189, v[94:97] offset:34816
	s_waitcnt vmcnt(2)
	ds_write_b128 v188, v[98:101]
	s_waitcnt vmcnt(1)
	ds_write_b128 v188, v[102:105] offset:34816
	s_nop 5
	v_mul_f32_e64 v180, v128, v180
	v_mul_f32_e64 v181, v129, v181
	v_mul_f32_e32 v178, v124, v178
	v_mul_f32_e32 v179, v125, v179
	v_fma_f32 v180, v126, v204, v180
	v_fma_f32 v181, v127, v205, v181
	v_fma_f32 v178, v122, v202, v178
	v_fma_f32 v179, v123, v203, v179
	v_mul_f32_e32 v200, v128, v200
	v_mul_f32_e32 v201, v129, v201
	v_mul_f32_e32 v198, v124, v198
	v_mul_f32_e32 v199, v125, v199
	v_fma_f32 v196, v126, v196, v200
	v_fma_f32 v197, v127, v197, v201
	v_fma_f32 v194, v122, v194, v198
	v_fma_f32 v195, v123, v195, v199
	v_cvt_pk_bf16_f32 v178, v178, v179
	v_cvt_pk_bf16_f32 v179, v180, v181
	v_cvt_pk_bf16_f32 v180, v194, v195
	v_cvt_pk_bf16_f32 v181, v196, v197
	global_store_dwordx2 v[218:219], v[178:179], off
	global_store_dwordx2 v[218:219], v[180:181], off offset:32

; #define GAS __attribute__((address_space(1)))
; __device__ __forceinline__ unsigned pk2(float lo, float hi) { const f32x2_t v = {lo, hi}; const bf16x2_t b = __builtin_convertvector(v, bf16x2_t); return __builtin_bit_cast(unsigned, b); }
; template <bool HG>
; __device__ __forceinline__ void readout_phase(const Args& a, Frame& F, const float* gain, int nrows) {
;     ...
;     for (int r = gw; r < nrows; r += NGW) {
;         const GAS v2u* f = (const GAS v2u*)(OF + (size_t)r * D) + F.lane; const GAS v2u* bk = (const GAS v2u*)(OB + (size_t)r * D) + F.lane;
;         const GAS v2u* g8 = (const GAS v2u*)(G + (size_t)r * D) + F.lane;
;         f32x4 v[8]; float ssj[8]; float tot = 0.f;
; #pragma unroll
;         for (int j = 0; j < 8; ++j) { const v2u fa = EW_NT ? __builtin_nontemporal_load(f + 64 * j) : f[64 * j], fb = EW_NT ? __builtin_nontemporal_load(bk + 64 * j) : bk[64 * j]; v[j] = (f32x4){bflo(fa.x) + bflo(fb.x), bfhi(fa.x) + bfhi(fb.x), bflo(fa.y) + bflo(fb.y), bfhi(fa.y) + bfhi(fb.y)}; ssj[j] = (v[j][0] * v[j][0] + v[j][1] * v[j][1]) + (v[j][2] * v[j][2] + v[j][3] * v[j][3]); tot += ssj[j]; }
;         float rs_all = 0.f;
;         if (HG) rs_all = 1.0f / sqrtf(wave_sum(tot) * (1.0f / D) + EPS);
;         GAS v2u* o8 = (GAS v2u*)(HN + (size_t)r * D) + F.lane;
; #pragma unroll
;         for (int j = 0; j < 8; ++j) {
;             float rs = rs_all; f32x4 gn = {1.f, 1.f, 1.f, 1.f};
;             if (!HG) rs = 1.0f / sqrtf(wave_sum(ssj[j]) * (1.0f / 256.0f) + EPS);
;             else gn = *(const GAS f32x4*)(gain + 256 * j + 4 * F.lane);
;             const v2u gw2 = EW_NT ? __builtin_nontemporal_load(g8 + 64 * j) : g8[64 * j];
;             const f32x4 gt = {bflo(gw2.x), bfhi(gw2.x), bflo(gw2.y), bfhi(gw2.y)};
;             const f32x4 y = (v[j] * rs) * gn * gt;
;             v2u w; w.x = pk2(y[0], y[1]); w.y = pk2(y[2], y[3]); o8[64 * j] = w; }
.LBB0_859:
	v_lshl_add_u64 v[36:37], v[2:3], 0, v[0:1]
	v_add_co_u32_e32 v6, vcc, 0xf7800000, v36
	v_lshl_add_u64 v[4:5], v[36:37], 0, s[52:53]
	s_nop 0
	v_addc_co_u32_e32 v7, vcc, -1, v37, vcc
	global_load_dwordx2 v[6:7], v[6:7], off nt
	s_nop 0
	global_load_dwordx2 v[8:9], v[36:37], off nt
	s_mov_b32 s6, 0xe6800000
	s_mov_b32 s7, -1
	s_add_i32 s8, s8, s42
	v_lshl_add_u64 v[2:3], v[2:3], 0, s[74:75]
	s_cmp_lt_i32 s8, s47
	s_waitcnt vmcnt(1)
	v_lshlrev_b32_e32 v10, 16, v6
	v_and_b32_e32 v11, 0xffff0000, v6
	s_waitcnt vmcnt(0)
	v_lshlrev_b32_e32 v12, 16, v8
	v_and_b32_e32 v13, 0xffff0000, v8
	v_lshlrev_b32_e32 v6, 16, v7
	v_and_b32_e32 v7, 0xffff0000, v7
	v_lshlrev_b32_e32 v8, 16, v9
	v_and_b32_e32 v9, 0xffff0000, v9
	v_add_f32_e32 v38, v10, v12
	v_add_f32_e32 v39, v11, v13
	v_add_f32_e32 v40, v6, v8
	v_add_f32_e32 v41, v7, v9
	v_mov_b32_e32 v8, v39
	v_mov_b32_e32 v9, v41
	v_mov_b32_e32 v6, v38
	v_mov_b32_e32 v7, v40
	v_mul_f32_e32 v8, v8, v8
	v_mul_f32_e32 v9, v9, v9
	s_nop 0
	v_fma_f32 v6, v6, v6, v8
	v_fma_f32 v7, v7, v7, v9
	s_nop 0
	v_add_f32_e32 v45, v6, v7
	global_load_dwordx2 v[6:7], v[4:5], off offset:512 nt
	global_load_dwordx2 v[8:9], v[36:37], off offset:512 nt
	v_add_f32_dpp v45, v45, v45 quad_perm:[1,0,3,2] row_mask:0xf bank_mask:0xf bound_ctrl:1
	s_waitcnt vmcnt(1)
	v_lshlrev_b32_e32 v10, 16, v6
	v_and_b32_e32 v11, 0xffff0000, v6
	s_waitcnt vmcnt(0)
	v_lshlrev_b32_e32 v12, 16, v8
	v_and_b32_e32 v13, 0xffff0000, v8
	v_lshlrev_b32_e32 v6, 16, v7
	v_and_b32_e32 v7, 0xffff0000, v7
	v_lshlrev_b32_e32 v8, 16, v9
	v_and_b32_e32 v9, 0xffff0000, v9
	v_add_f32_e32 v32, v10, v12
	v_add_f32_e32 v33, v11, v13
	v_add_f32_e32 v34, v6, v8
	v_add_f32_e32 v35, v7, v9
	v_mov_b32_e32 v8, v33
	v_mov_b32_e32 v9, v35
	v_mov_b32_e32 v6, v32
	v_mov_b32_e32 v7, v34
	v_mul_f32_e32 v8, v8, v8
	v_mul_f32_e32 v9, v9, v9
	v_add_f32_dpp v45, v45, v45 quad_perm:[2,3,0,1] row_mask:0xf bank_mask:0xf bound_ctrl:1
	v_fma_f32 v6, v6, v6, v8
	v_fma_f32 v7, v7, v7, v9
	s_nop 0
	v_add_f32_e32 v52, v6, v7
	global_load_dwordx2 v[6:7], v[4:5], off offset:1024 nt
	global_load_dwordx2 v[8:9], v[36:37], off offset:1024 nt
	v_add_f32_dpp v45, v45, v45 row_half_mirror row_mask:0xf bank_mask:0xf bound_ctrl:1
	s_waitcnt vmcnt(1)
	v_lshlrev_b32_e32 v10, 16, v6
	v_and_b32_e32 v11, 0xffff0000, v6
	s_waitcnt vmcnt(0)
	v_lshlrev_b32_e32 v12, 16, v8
	v_and_b32_e32 v13, 0xffff0000, v8
	v_lshlrev_b32_e32 v6, 16, v7
	v_and_b32_e32 v7, 0xffff0000, v7
	v_lshlrev_b32_e32 v8, 16, v9
	v_and_b32_e32 v9, 0xffff0000, v9
	v_add_f32_e32 v26, v10, v12
	v_add_f32_e32 v27, v11, v13
	v_add_f32_e32 v28, v6, v8
	v_add_f32_e32 v29, v7, v9
	v_mov_b32_e32 v8, v27
	v_mov_b32_e32 v9, v29
	v_mov_b32_e32 v6, v26
	v_mov_b32_e32 v7, v28
	v_mul_f32_e32 v8, v8, v8
	v_mul_f32_e32 v9, v9, v9
	v_add_f32_dpp v45, v45, v45 row_mirror row_mask:0xf bank_mask:0xf bound_ctrl:1
	v_fma_f32 v6, v6, v6, v8
	v_fma_f32 v7, v7, v7, v9
	v_readlane_b32 s9, v45, 16
	v_add_f32_e32 v53, v6, v7
	global_load_dwordx2 v[6:7], v[4:5], off offset:1536 nt
	global_load_dwordx2 v[8:9], v[36:37], off offset:1536 nt
	v_readlane_b32 s10, v45, 48
	v_mov_b32_e32 v46, s9
	s_waitcnt vmcnt(1)
	v_lshlrev_b32_e32 v10, 16, v6
	v_and_b32_e32 v11, 0xffff0000, v6
	s_waitcnt vmcnt(0)
	v_lshlrev_b32_e32 v12, 16, v8
	v_and_b32_e32 v13, 0xffff0000, v8
	v_lshlrev_b32_e32 v6, 16, v7
	v_and_b32_e32 v7, 0xffff0000, v7
	v_lshlrev_b32_e32 v8, 16, v9
	v_and_b32_e32 v9, 0xffff0000, v9
	v_add_f32_e32 v20, v10, v12
	v_add_f32_e32 v21, v11, v13
	v_add_f32_e32 v22, v6, v8
	v_add_f32_e32 v23, v7, v9
	v_mov_b32_e32 v8, v21
	v_mov_b32_e32 v9, v23
	v_mov_b32_e32 v6, v20
	v_mov_b32_e32 v7, v22
	v_mul_f32_e32 v8, v8, v8
	v_mul_f32_e32 v9, v9, v9
	v_mov_b32_e32 v47, s10
	v_fma_f32 v6, v6, v6, v8
	v_fma_f32 v7, v7, v7, v9
	s_nop 0
	v_add_f32_e32 v54, v6, v7
	global_load_dwordx2 v[6:7], v[4:5], off offset:2048 nt
	global_load_dwordx2 v[8:9], v[36:37], off offset:2048 nt
	s_waitcnt vmcnt(1)
	v_lshlrev_b32_e32 v10, 16, v6
	v_and_b32_e32 v11, 0xffff0000, v6
	s_waitcnt vmcnt(0)
	v_lshlrev_b32_e32 v12, 16, v8
	v_and_b32_e32 v13, 0xffff0000, v8
	v_lshlrev_b32_e32 v6, 16, v7
	v_and_b32_e32 v7, 0xffff0000, v7
	v_lshlrev_b32_e32 v8, 16, v9
	v_and_b32_e32 v9, 0xffff0000, v9
	v_add_f32_e32 v16, v10, v12
	v_add_f32_e32 v17, v11, v13
	v_add_f32_e32 v18, v6, v8
	v_add_f32_e32 v19, v7, v9
	v_mov_b32_e32 v8, v17
	v_mov_b32_e32 v9, v19
	v_mov_b32_e32 v6, v16
	v_mov_b32_e32 v7, v18
	v_mul_f32_e32 v8, v8, v8
	v_mul_f32_e32 v9, v9, v9
	s_nop 0
	v_fma_f32 v6, v6, v6, v8
	v_fma_f32 v7, v7, v7, v9
	s_nop 0
	v_add_f32_e32 v55, v6, v7
	global_load_dwordx2 v[6:7], v[4:5], off offset:2560 nt
	global_load_dwordx2 v[8:9], v[36:37], off offset:2560 nt
	s_waitcnt vmcnt(1)
	v_lshlrev_b32_e32 v10, 16, v6
	v_and_b32_e32 v11, 0xffff0000, v6
	s_waitcnt vmcnt(0)
	v_lshlrev_b32_e32 v12, 16, v8
	v_and_b32_e32 v13, 0xffff0000, v8
	v_lshlrev_b32_e32 v6, 16, v7
	v_and_b32_e32 v7, 0xffff0000, v7
	v_lshlrev_b32_e32 v8, 16, v9
	v_and_b32_e32 v9, 0xffff0000, v9
	v_add_f32_e32 v12, v10, v12
	v_add_f32_e32 v13, v11, v13
	v_add_f32_e32 v14, v6, v8
	v_add_f32_e32 v15, v7, v9
	v_mov_b32_e32 v8, v13
	v_mov_b32_e32 v9, v15
	v_mov_b32_e32 v6, v12
	v_mov_b32_e32 v7, v14
	v_mul_f32_e32 v8, v8, v8
	v_mul_f32_e32 v9, v9, v9
	s_nop 0
	v_fma_f32 v6, v6, v6, v8
	v_fma_f32 v7, v7, v7, v9
	s_nop 0
	v_add_f32_e32 v44, v6, v7
	global_load_dwordx2 v[6:7], v[4:5], off offset:3072 nt
	global_load_dwordx2 v[10:11], v[36:37], off offset:3072 nt
	s_waitcnt vmcnt(1)
	v_lshlrev_b32_e32 v8, 16, v6
	v_and_b32_e32 v9, 0xffff0000, v6
	s_waitcnt vmcnt(0)
; #define GAS __attribute__((address_space(1)))
; __device__ __forceinline__ unsigned pk2(float lo, float hi) { const f32x2_t v = {lo, hi}; const bf16x2_t b = __builtin_convertvector(v, bf16x2_t); return __builtin_bit_cast(unsigned, b); }
; template <bool HG>
; __device__ __forceinline__ void readout_phase(const Args& a, Frame& F, const float* gain, int nrows) {
;     ...
;     for (int r = gw; r < nrows; r += NGW) {
;         const GAS v2u* f = (const GAS v2u*)(OF + (size_t)r * D) + F.lane; const GAS v2u* bk = (const GAS v2u*)(OB + (size_t)r * D) + F.lane;
;         const GAS v2u* g8 = (const GAS v2u*)(G + (size_t)r * D) + F.lane;
;         f32x4 v[8]; float ssj[8]; float tot = 0.f;
; #pragma unroll
;         for (int j = 0; j < 8; ++j) { const v2u fa = EW_NT ? __builtin_nontemporal_load(f + 64 * j) : f[64 * j], fb = EW_NT ? __builtin_nontemporal_load(bk + 64 * j) : bk[64 * j]; v[j] = (f32x4){bflo(fa.x) + bflo(fb.x), bfhi(fa.x) + bfhi(fb.x), bflo(fa.y) + bflo(fb.y), bfhi(fa.y) + bfhi(fb.y)}; ssj[j] = (v[j][0] * v[j][0] + v[j][1] * v[j][1]) + (v[j][2] * v[j][2] + v[j][3] * v[j][3]); tot += ssj[j]; }
;         float rs_all = 0.f;
;         if (HG) rs_all = 1.0f / sqrtf(wave_sum(tot) * (1.0f / D) + EPS);
;         GAS v2u* o8 = (GAS v2u*)(HN + (size_t)r * D) + F.lane;
; #pragma unroll
;         for (int j = 0; j < 8; ++j) {
;             float rs = rs_all; f32x4 gn = {1.f, 1.f, 1.f, 1.f};
;             if (!HG) rs = 1.0f / sqrtf(wave_sum(ssj[j]) * (1.0f / 256.0f) + EPS);
;             else gn = *(const GAS f32x4*)(gain + 256 * j + 4 * F.lane);
;             const v2u gw2 = EW_NT ? __builtin_nontemporal_load(g8 + 64 * j) : g8[64 * j];
;             const f32x4 gt = {bflo(gw2.x), bfhi(gw2.x), bflo(gw2.y), bfhi(gw2.y)};
;             const f32x4 y = (v[j] * rs) * gn * gt;
;             v2u w; w.x = pk2(y[0], y[1]); w.y = pk2(y[2], y[3]); o8[64 * j] = w; }
	v_lshlrev_b32_e32 v24, 16, v10
	v_and_b32_e32 v25, 0xffff0000, v10
	v_lshlrev_b32_e32 v6, 16, v7
	v_and_b32_e32 v7, 0xffff0000, v7
	v_lshlrev_b32_e32 v10, 16, v11
	v_and_b32_e32 v11, 0xffff0000, v11
	v_add_f32_e32 v8, v8, v24
	v_add_f32_e32 v9, v9, v25
	v_add_f32_e32 v10, v6, v10
	v_add_f32_e32 v11, v7, v11
	v_mov_b32_e32 v24, v9
	v_mov_b32_e32 v25, v11
	v_mov_b32_e32 v6, v8
	v_mov_b32_e32 v7, v10
	v_mul_f32_e32 v24, v24, v24
	v_mul_f32_e32 v25, v25, v25
	s_nop 0
	v_fma_f32 v6, v6, v6, v24
	v_fma_f32 v7, v7, v7, v25
	s_nop 0
	v_add_f32_e32 v43, v6, v7
	global_load_dwordx2 v[6:7], v[4:5], off offset:3584 nt
	global_load_dwordx2 v[24:25], v[36:37], off offset:3584 nt
	s_waitcnt vmcnt(1)
	v_lshlrev_b32_e32 v4, 16, v6
	v_and_b32_e32 v5, 0xffff0000, v6
	s_waitcnt vmcnt(0)
	v_lshlrev_b32_e32 v30, 16, v24
	v_and_b32_e32 v31, 0xffff0000, v24
	v_lshlrev_b32_e32 v6, 16, v7
	v_and_b32_e32 v7, 0xffff0000, v7
	v_lshlrev_b32_e32 v24, 16, v25
	v_and_b32_e32 v25, 0xffff0000, v25
	v_add_f32_e32 v4, v4, v30
	v_add_f32_e32 v5, v5, v31
	v_add_f32_e32 v6, v6, v24
	v_add_f32_e32 v7, v7, v25
	v_mov_b32_e32 v30, v5
	v_mov_b32_e32 v31, v7
	v_mov_b32_e32 v24, v4
	v_mov_b32_e32 v25, v6
	v_mul_f32_e32 v30, v30, v30
	v_mul_f32_e32 v31, v31, v31
	s_nop 0
	v_fma_f32 v24, v24, v24, v30
	v_fma_f32 v25, v25, v25, v31
	v_lshl_add_u64 v[30:31], v[36:37], 0, s[6:7]
	v_readlane_b32 s6, v45, 0
	v_readlane_b32 s7, v45, 32
	v_add_f32_e32 v42, v24, v25
	v_lshl_add_u64 v[24:25], v[36:37], 0, s[12:13]
	v_add_f32_e32 v46, s6, v46
	v_add_f32_e32 v47, s7, v47
	s_nop 0
	v_add_f32_e32 v45, v46, v47
	v_fmamk_f32 v45, v45, 0x3b800000, v252
	v_cmp_gt_f32_e32 vcc, s55, v45
	v_mul_f32_e32 v46, 0x4f800000, v45
	s_nop 0
	v_cndmask_b32_e32 v45, v45, v46, vcc
	v_sqrt_f32_e32 v46, v45
	s_nop 0
	v_add_u32_e32 v47, -1, v46
	v_fma_f32 v48, -v47, v46, v45
	v_cmp_ge_f32_e64 s[6:7], 0, v48
	v_add_u32_e32 v48, 1, v46
	s_nop 0
	v_cndmask_b32_e64 v47, v46, v47, s[6:7]
	v_fma_f32 v46, -v48, v46, v45
	v_cmp_lt_f32_e64 s[6:7], 0, v46
	s_nop 1
	v_cndmask_b32_e64 v46, v47, v48, s[6:7]
	v_mul_f32_e32 v47, 0x37800000, v46
	v_cndmask_b32_e32 v46, v46, v47, vcc
	v_cmp_class_f32_e32 vcc, v45, v253
	s_nop 1
	v_cndmask_b32_e32 v45, v46, v45, vcc
	v_div_scale_f32 v46, s[6:7], v45, v45, 1.0
	v_rcp_f32_e32 v47, v46
	s_mov_b32 s6, 0xe6800000
	v_fma_f32 v48, -v46, v47, 1.0
	v_fmac_f32_e32 v47, v48, v47
	v_div_scale_f32 v48, vcc, 1.0, v45, 1.0
	v_mul_f32_e32 v49, v48, v47
	v_fma_f32 v50, -v46, v49, v48
	v_fmac_f32_e32 v49, v50, v47
	v_fma_f32 v46, -v46, v49, v48
	v_div_fmas_f32 v46, v46, v47, v49
	v_add_co_u32_e32 v48, vcc, s6, v36
	v_div_fixup_f32 v46, v46, v45, 1.0
	s_nop 0
	v_addc_co_u32_e32 v49, vcc, -1, v37, vcc
	global_load_dwordx2 v[48:49], v[48:49], off nt
	v_mul_f32_e32 v38, v38, v46
	v_mul_f32_e32 v39, v39, v46
	v_mul_f32_e32 v40, v40, v46
	v_mul_f32_e32 v41, v41, v46
	v_add_co_u32_e32 v36, vcc, s67, v36
	s_waitcnt vmcnt(0)
	v_lshlrev_b32_e32 v50, 16, v48
	v_and_b32_e32 v51, 0xffff0000, v48
	v_lshlrev_b32_e32 v48, 16, v49
	v_and_b32_e32 v49, 0xffff0000, v49
	v_mul_f32_e32 v40, v40, v48
	v_mul_f32_e32 v41, v41, v49
	v_mul_f32_e32 v38, v38, v50
	v_mul_f32_e32 v39, v39, v51
	v_addc_co_u32_e32 v37, vcc, -1, v37, vcc
	v_cvt_pk_bf16_f32 v38, v38, v39
	v_cvt_pk_bf16_f32 v39, v40, v41
	global_store_dwordx2 v[36:37], v[38:39], off
	v_add_f32_dpp v36, v52, v52 quad_perm:[1,0,3,2] row_mask:0xf bank_mask:0xf bound_ctrl:1
	s_nop 1
	v_add_f32_dpp v36, v36, v36 quad_perm:[2,3,0,1] row_mask:0xf bank_mask:0xf bound_ctrl:1
	s_nop 1
	v_add_f32_dpp v36, v36, v36 row_half_mirror row_mask:0xf bank_mask:0xf bound_ctrl:1
	s_nop 1
	v_add_f32_dpp v36, v36, v36 row_mirror row_mask:0xf bank_mask:0xf bound_ctrl:1
	s_nop 0
	v_readlane_b32 s9, v36, 16
	v_readlane_b32 s10, v36, 48
	v_readlane_b32 s6, v36, 0
	v_readlane_b32 s7, v36, 32
	v_mov_b32_e32 v36, s9
	v_mov_b32_e32 v37, s10
	v_add_f32_e32 v36, s6, v36
	v_add_f32_e32 v37, s7, v37
	s_nop 0
	v_add_f32_e32 v36, v36, v37
	v_fmamk_f32 v36, v36, 0x3b800000, v252
	v_cmp_gt_f32_e32 vcc, s55, v36
	v_mul_f32_e32 v37, 0x4f800000, v36
	s_nop 0
	v_cndmask_b32_e32 v36, v36, v37, vcc
	v_sqrt_f32_e32 v37, v36
	s_nop 0
	v_add_u32_e32 v38, -1, v37
	v_fma_f32 v39, -v38, v37, v36
	v_cmp_ge_f32_e64 s[6:7], 0, v39
	v_add_u32_e32 v39, 1, v37
	s_nop 0
	v_cndmask_b32_e64 v38, v37, v38, s[6:7]
	v_fma_f32 v37, -v39, v37, v36
	v_cmp_lt_f32_e64 s[6:7], 0, v37
	s_nop 1
	v_cndmask_b32_e64 v37, v38, v39, s[6:7]
	v_mul_f32_e32 v38, 0x37800000, v37
	v_cndmask_b32_e32 v37, v37, v38, vcc
	v_cmp_class_f32_e32 vcc, v36, v253
	s_nop 1
	v_cndmask_b32_e32 v36, v37, v36, vcc
	v_div_scale_f32 v37, s[6:7], v36, v36, 1.0
	v_rcp_f32_e32 v38, v37
	s_nop 0
	v_fma_f32 v39, -v37, v38, 1.0
	v_fmac_f32_e32 v38, v39, v38
	v_div_scale_f32 v39, vcc, 1.0, v36, 1.0
	v_mul_f32_e32 v40, v39, v38
	v_fma_f32 v41, -v37, v40, v39
	v_fmac_f32_e32 v40, v41, v38
	v_fma_f32 v37, -v37, v40, v39
	v_div_fmas_f32 v37, v37, v38, v40
	global_load_dwordx2 v[38:39], v[30:31], off offset:512 nt
	v_div_fixup_f32 v36, v37, v36, 1.0
	v_mul_f32_e32 v32, v32, v36
	v_mul_f32_e32 v33, v33, v36
	v_mul_f32_e32 v34, v34, v36
	v_mul_f32_e32 v35, v35, v36
	s_waitcnt vmcnt(0)
; #define GAS __attribute__((address_space(1)))
; __device__ __forceinline__ unsigned pk2(float lo, float hi) { const f32x2_t v = {lo, hi}; const bf16x2_t b = __builtin_convertvector(v, bf16x2_t); return __builtin_bit_cast(unsigned, b); }
; template <bool HG>
; __device__ __forceinline__ void readout_phase(const Args& a, Frame& F, const float* gain, int nrows) {
;     ...
; #pragma unroll
;         for (int j = 0; j < 8; ++j) {
;             float rs = rs_all; f32x4 gn = {1.f, 1.f, 1.f, 1.f};
;             if (!HG) rs = 1.0f / sqrtf(wave_sum(ssj[j]) * (1.0f / 256.0f) + EPS);
;             else gn = *(const GAS f32x4*)(gain + 256 * j + 4 * F.lane);
;             const v2u gw2 = EW_NT ? __builtin_nontemporal_load(g8 + 64 * j) : g8[64 * j];
;             const f32x4 gt = {bflo(gw2.x), bfhi(gw2.x), bflo(gw2.y), bfhi(gw2.y)};
;             const f32x4 y = (v[j] * rs) * gn * gt;
;             v2u w; w.x = pk2(y[0], y[1]); w.y = pk2(y[2], y[3]); o8[64 * j] = w; }
	v_lshlrev_b32_e32 v40, 16, v38
	v_and_b32_e32 v41, 0xffff0000, v38
	v_lshlrev_b32_e32 v38, 16, v39
	v_and_b32_e32 v39, 0xffff0000, v39
	v_mul_f32_e32 v34, v34, v38
	v_mul_f32_e32 v35, v35, v39
	v_mul_f32_e32 v32, v32, v40
	v_mul_f32_e32 v33, v33, v41
	s_nop 0
	v_cvt_pk_bf16_f32 v32, v32, v33
	v_cvt_pk_bf16_f32 v33, v34, v35
	global_store_dwordx2 v[24:25], v[32:33], off offset:512
	v_add_f32_dpp v32, v53, v53 quad_perm:[1,0,3,2] row_mask:0xf bank_mask:0xf bound_ctrl:1
	s_nop 1
	v_add_f32_dpp v32, v32, v32 quad_perm:[2,3,0,1] row_mask:0xf bank_mask:0xf bound_ctrl:1
	s_nop 1
	v_add_f32_dpp v32, v32, v32 row_half_mirror row_mask:0xf bank_mask:0xf bound_ctrl:1
	s_nop 1
	v_add_f32_dpp v32, v32, v32 row_mirror row_mask:0xf bank_mask:0xf bound_ctrl:1
	s_nop 0
	v_readlane_b32 s9, v32, 16
	v_readlane_b32 s10, v32, 48
	v_readlane_b32 s6, v32, 0
	v_readlane_b32 s7, v32, 32
	v_mov_b32_e32 v32, s9
	v_mov_b32_e32 v33, s10
	v_add_f32_e32 v32, s6, v32
	v_add_f32_e32 v33, s7, v33
	s_nop 0
	v_add_f32_e32 v32, v32, v33
	v_fmamk_f32 v32, v32, 0x3b800000, v252
	v_cmp_gt_f32_e32 vcc, s55, v32
	v_mul_f32_e32 v33, 0x4f800000, v32
	s_nop 0
	v_cndmask_b32_e32 v32, v32, v33, vcc
	v_sqrt_f32_e32 v33, v32
	s_nop 0
	v_add_u32_e32 v34, -1, v33
	v_fma_f32 v35, -v34, v33, v32
	v_cmp_ge_f32_e64 s[6:7], 0, v35
	v_add_u32_e32 v35, 1, v33
	s_nop 0
	v_cndmask_b32_e64 v34, v33, v34, s[6:7]
	v_fma_f32 v33, -v35, v33, v32
	v_cmp_lt_f32_e64 s[6:7], 0, v33
	s_nop 1
	v_cndmask_b32_e64 v33, v34, v35, s[6:7]
	v_mul_f32_e32 v34, 0x37800000, v33
	v_cndmask_b32_e32 v33, v33, v34, vcc
	v_cmp_class_f32_e32 vcc, v32, v253
	s_nop 1
	v_cndmask_b32_e32 v32, v33, v32, vcc
	v_div_scale_f32 v33, s[6:7], v32, v32, 1.0
	v_rcp_f32_e32 v34, v33
	s_nop 0
	v_fma_f32 v35, -v33, v34, 1.0
	v_fmac_f32_e32 v34, v35, v34
	v_div_scale_f32 v35, vcc, 1.0, v32, 1.0
	v_mul_f32_e32 v36, v35, v34
	v_fma_f32 v37, -v33, v36, v35
	v_fmac_f32_e32 v36, v37, v34
	v_fma_f32 v33, -v33, v36, v35
	v_div_fmas_f32 v33, v33, v34, v36
	global_load_dwordx2 v[34:35], v[30:31], off offset:1024 nt
	v_div_fixup_f32 v32, v33, v32, 1.0
	v_mul_f32_e32 v26, v26, v32
	v_mul_f32_e32 v27, v27, v32
	v_mul_f32_e32 v28, v28, v32
	v_mul_f32_e32 v29, v29, v32
	s_waitcnt vmcnt(0)
	v_lshlrev_b32_e32 v36, 16, v34
	v_and_b32_e32 v37, 0xffff0000, v34
	v_lshlrev_b32_e32 v34, 16, v35
	v_and_b32_e32 v35, 0xffff0000, v35
	v_mul_f32_e32 v28, v28, v34
	v_mul_f32_e32 v29, v29, v35
	v_mul_f32_e32 v26, v26, v36
	v_mul_f32_e32 v27, v27, v37
	s_nop 0
	v_cvt_pk_bf16_f32 v26, v26, v27
	v_cvt_pk_bf16_f32 v27, v28, v29
	global_store_dwordx2 v[24:25], v[26:27], off offset:1024
	v_add_f32_dpp v26, v54, v54 quad_perm:[1,0,3,2] row_mask:0xf bank_mask:0xf bound_ctrl:1
	s_nop 1
	v_add_f32_dpp v26, v26, v26 quad_perm:[2,3,0,1] row_mask:0xf bank_mask:0xf bound_ctrl:1
	s_nop 1
	v_add_f32_dpp v26, v26, v26 row_half_mirror row_mask:0xf bank_mask:0xf bound_ctrl:1
	s_nop 1
	v_add_f32_dpp v26, v26, v26 row_mirror row_mask:0xf bank_mask:0xf bound_ctrl:1
	s_nop 0
	v_readlane_b32 s9, v26, 16
	v_readlane_b32 s10, v26, 48
	v_readlane_b32 s6, v26, 0
	v_readlane_b32 s7, v26, 32
	v_mov_b32_e32 v26, s9
	v_mov_b32_e32 v27, s10
	v_add_f32_e32 v26, s6, v26
	v_add_f32_e32 v27, s7, v27
	s_nop 0
	v_add_f32_e32 v26, v26, v27
	v_fmamk_f32 v26, v26, 0x3b800000, v252
	v_cmp_gt_f32_e32 vcc, s55, v26
	v_mul_f32_e32 v27, 0x4f800000, v26
	s_nop 0
	v_cndmask_b32_e32 v26, v26, v27, vcc
	v_sqrt_f32_e32 v27, v26
	s_nop 0
	v_add_u32_e32 v28, -1, v27
	v_fma_f32 v29, -v28, v27, v26
	v_cmp_ge_f32_e64 s[6:7], 0, v29
	v_add_u32_e32 v29, 1, v27
	s_nop 0
	v_cndmask_b32_e64 v28, v27, v28, s[6:7]
	v_fma_f32 v27, -v29, v27, v26
	v_cmp_lt_f32_e64 s[6:7], 0, v27
	s_nop 1
	v_cndmask_b32_e64 v27, v28, v29, s[6:7]
	v_mul_f32_e32 v28, 0x37800000, v27
	v_cndmask_b32_e32 v27, v27, v28, vcc
	v_cmp_class_f32_e32 vcc, v26, v253
	s_nop 1
	v_cndmask_b32_e32 v26, v27, v26, vcc
	v_div_scale_f32 v27, s[6:7], v26, v26, 1.0
	v_rcp_f32_e32 v28, v27
	s_nop 0
	v_fma_f32 v29, -v27, v28, 1.0
	v_fmac_f32_e32 v28, v29, v28
	v_div_scale_f32 v29, vcc, 1.0, v26, 1.0
	v_mul_f32_e32 v32, v29, v28
	v_fma_f32 v33, -v27, v32, v29
	v_fmac_f32_e32 v32, v33, v28
	v_fma_f32 v27, -v27, v32, v29
	v_div_fmas_f32 v27, v27, v28, v32
	global_load_dwordx2 v[28:29], v[30:31], off offset:1536 nt
	v_div_fixup_f32 v26, v27, v26, 1.0
	v_mul_f32_e32 v20, v20, v26
	v_mul_f32_e32 v21, v21, v26
	v_mul_f32_e32 v22, v22, v26
	v_mul_f32_e32 v23, v23, v26
	s_waitcnt vmcnt(0)
	v_lshlrev_b32_e32 v32, 16, v28
	v_and_b32_e32 v33, 0xffff0000, v28
	v_lshlrev_b32_e32 v28, 16, v29
	v_and_b32_e32 v29, 0xffff0000, v29
	v_mul_f32_e32 v22, v22, v28
	v_mul_f32_e32 v23, v23, v29
	v_mul_f32_e32 v20, v20, v32
	v_mul_f32_e32 v21, v21, v33
	s_nop 0
	v_cvt_pk_bf16_f32 v20, v20, v21
	v_cvt_pk_bf16_f32 v21, v22, v23
	global_store_dwordx2 v[24:25], v[20:21], off offset:1536
	v_add_f32_dpp v20, v55, v55 quad_perm:[1,0,3,2] row_mask:0xf bank_mask:0xf bound_ctrl:1
	s_nop 1
	v_add_f32_dpp v20, v20, v20 quad_perm:[2,3,0,1] row_mask:0xf bank_mask:0xf bound_ctrl:1
	s_nop 1
	v_add_f32_dpp v20, v20, v20 row_half_mirror row_mask:0xf bank_mask:0xf bound_ctrl:1
	s_nop 1
	v_add_f32_dpp v20, v20, v20 row_mirror row_mask:0xf bank_mask:0xf bound_ctrl:1
	s_nop 0
	v_readlane_b32 s9, v20, 16
	v_readlane_b32 s10, v20, 48
	v_readlane_b32 s6, v20, 0
	v_readlane_b32 s7, v20, 32
	v_mov_b32_e32 v20, s9
	v_mov_b32_e32 v21, s10
	v_add_f32_e32 v20, s6, v20
	v_add_f32_e32 v21, s7, v21
	s_nop 0
	v_add_f32_e32 v20, v20, v21
	v_fmamk_f32 v20, v20, 0x3b800000, v252
	v_cmp_gt_f32_e32 vcc, s55, v20
	v_mul_f32_e32 v21, 0x4f800000, v20
	s_nop 0
	v_cndmask_b32_e32 v20, v20, v21, vcc
	v_sqrt_f32_e32 v21, v20
	s_nop 0
	v_add_u32_e32 v22, -1, v21
	v_fma_f32 v23, -v22, v21, v20
	v_cmp_ge_f32_e64 s[6:7], 0, v23
	v_add_u32_e32 v23, 1, v21
	s_nop 0
	v_cndmask_b32_e64 v22, v21, v22, s[6:7]
	v_fma_f32 v21, -v23, v21, v20
	v_cmp_lt_f32_e64 s[6:7], 0, v21
	s_nop 1
	v_cndmask_b32_e64 v21, v22, v23, s[6:7]
	v_mul_f32_e32 v22, 0x37800000, v21
	v_cndmask_b32_e32 v21, v21, v22, vcc
	v_cmp_class_f32_e32 vcc, v20, v253
	s_nop 1
	v_cndmask_b32_e32 v20, v21, v20, vcc
	v_div_scale_f32 v21, s[6:7], v20, v20, 1.0
	v_rcp_f32_e32 v22, v21
	s_nop 0
	v_fma_f32 v23, -v21, v22, 1.0
	v_fmac_f32_e32 v22, v23, v22
	v_div_scale_f32 v23, vcc, 1.0, v20, 1.0
	v_mul_f32_e32 v26, v23, v22
	v_fma_f32 v27, -v21, v26, v23
	v_fmac_f32_e32 v26, v27, v22
	v_fma_f32 v21, -v21, v26, v23
	v_div_fmas_f32 v21, v21, v22, v26
	global_load_dwordx2 v[22:23], v[30:31], off offset:2048 nt
	v_div_fixup_f32 v20, v21, v20, 1.0
	v_mul_f32_e32 v16, v16, v20
	v_mul_f32_e32 v17, v17, v20
	v_mul_f32_e32 v18, v18, v20
	v_mul_f32_e32 v19, v19, v20
	s_waitcnt vmcnt(0)
; #define GAS __attribute__((address_space(1)))
; __device__ __forceinline__ unsigned pk2(float lo, float hi) { const f32x2_t v = {lo, hi}; const bf16x2_t b = __builtin_convertvector(v, bf16x2_t); return __builtin_bit_cast(unsigned, b); }
; template <bool HG>
; __device__ __forceinline__ void readout_phase(const Args& a, Frame& F, const float* gain, int nrows) {
;     ...
;     for (int r = gw; r < nrows; r += NGW) {
;         const GAS v2u* f = (const GAS v2u*)(OF + (size_t)r * D) + F.lane; const GAS v2u* bk = (const GAS v2u*)(OB + (size_t)r * D) + F.lane;
;         const GAS v2u* g8 = (const GAS v2u*)(G + (size_t)r * D) + F.lane;
;         f32x4 v[8]; float ssj[8]; float tot = 0.f;
; #pragma unroll
;         for (int j = 0; j < 8; ++j) { const v2u fa = EW_NT ? __builtin_nontemporal_load(f + 64 * j) : f[64 * j], fb = EW_NT ? __builtin_nontemporal_load(bk + 64 * j) : bk[64 * j]; v[j] = (f32x4){bflo(fa.x) + bflo(fb.x), bfhi(fa.x) + bfhi(fb.x), bflo(fa.y) + bflo(fb.y), bfhi(fa.y) + bfhi(fb.y)}; ssj[j] = (v[j][0] * v[j][0] + v[j][1] * v[j][1]) + (v[j][2] * v[j][2] + v[j][3] * v[j][3]); tot += ssj[j]; }
;         float rs_all = 0.f;
;         if (HG) rs_all = 1.0f / sqrtf(wave_sum(tot) * (1.0f / D) + EPS);
;         GAS v2u* o8 = (GAS v2u*)(HN + (size_t)r * D) + F.lane;
; #pragma unroll
;         for (int j = 0; j < 8; ++j) {
;             float rs = rs_all; f32x4 gn = {1.f, 1.f, 1.f, 1.f};
;             if (!HG) rs = 1.0f / sqrtf(wave_sum(ssj[j]) * (1.0f / 256.0f) + EPS);
;             else gn = *(const GAS f32x4*)(gain + 256 * j + 4 * F.lane);
;             const v2u gw2 = EW_NT ? __builtin_nontemporal_load(g8 + 64 * j) : g8[64 * j];
;             const f32x4 gt = {bflo(gw2.x), bfhi(gw2.x), bflo(gw2.y), bfhi(gw2.y)};
;             const f32x4 y = (v[j] * rs) * gn * gt;
;             v2u w; w.x = pk2(y[0], y[1]); w.y = pk2(y[2], y[3]); o8[64 * j] = w; }
	v_lshlrev_b32_e32 v26, 16, v22
	v_and_b32_e32 v27, 0xffff0000, v22
	v_lshlrev_b32_e32 v22, 16, v23
	v_and_b32_e32 v23, 0xffff0000, v23
	v_mul_f32_e32 v18, v18, v22
	v_mul_f32_e32 v19, v19, v23
	v_mul_f32_e32 v16, v16, v26
	v_mul_f32_e32 v17, v17, v27
	s_nop 0
	v_cvt_pk_bf16_f32 v16, v16, v17
	v_cvt_pk_bf16_f32 v17, v18, v19
	global_store_dwordx2 v[24:25], v[16:17], off offset:2048
	v_add_f32_dpp v16, v44, v44 quad_perm:[1,0,3,2] row_mask:0xf bank_mask:0xf bound_ctrl:1
	s_nop 1
	v_add_f32_dpp v16, v16, v16 quad_perm:[2,3,0,1] row_mask:0xf bank_mask:0xf bound_ctrl:1
	s_nop 1
	v_add_f32_dpp v16, v16, v16 row_half_mirror row_mask:0xf bank_mask:0xf bound_ctrl:1
	s_nop 1
	v_add_f32_dpp v16, v16, v16 row_mirror row_mask:0xf bank_mask:0xf bound_ctrl:1
	s_nop 0
	v_readlane_b32 s9, v16, 16
	v_readlane_b32 s10, v16, 48
	v_readlane_b32 s6, v16, 0
	v_readlane_b32 s7, v16, 32
	v_mov_b32_e32 v16, s9
	v_mov_b32_e32 v17, s10
	v_add_f32_e32 v16, s6, v16
	v_add_f32_e32 v17, s7, v17
	s_nop 0
	v_add_f32_e32 v16, v16, v17
	v_fmamk_f32 v16, v16, 0x3b800000, v252
	v_cmp_gt_f32_e32 vcc, s55, v16
	v_mul_f32_e32 v17, 0x4f800000, v16
	s_nop 0
	v_cndmask_b32_e32 v16, v16, v17, vcc
	v_sqrt_f32_e32 v17, v16
	s_nop 0
	v_add_u32_e32 v18, -1, v17
	v_fma_f32 v19, -v18, v17, v16
	v_cmp_ge_f32_e64 s[6:7], 0, v19
	v_add_u32_e32 v19, 1, v17
	s_nop 0
	v_cndmask_b32_e64 v18, v17, v18, s[6:7]
	v_fma_f32 v17, -v19, v17, v16
	v_cmp_lt_f32_e64 s[6:7], 0, v17
	s_nop 1
	v_cndmask_b32_e64 v17, v18, v19, s[6:7]
	v_mul_f32_e32 v18, 0x37800000, v17
	v_cndmask_b32_e32 v17, v17, v18, vcc
	v_cmp_class_f32_e32 vcc, v16, v253
	s_nop 1
	v_cndmask_b32_e32 v16, v17, v16, vcc
	v_div_scale_f32 v17, s[6:7], v16, v16, 1.0
	v_rcp_f32_e32 v18, v17
	s_nop 0
	v_fma_f32 v19, -v17, v18, 1.0
	v_fmac_f32_e32 v18, v19, v18
	v_div_scale_f32 v19, vcc, 1.0, v16, 1.0
	v_mul_f32_e32 v20, v19, v18
	v_fma_f32 v21, -v17, v20, v19
	v_fmac_f32_e32 v20, v21, v18
	v_fma_f32 v17, -v17, v20, v19
	v_div_fmas_f32 v17, v17, v18, v20
	global_load_dwordx2 v[18:19], v[30:31], off offset:2560 nt
	v_div_fixup_f32 v16, v17, v16, 1.0
	v_mul_f32_e32 v12, v12, v16
	v_mul_f32_e32 v13, v13, v16
	v_mul_f32_e32 v14, v14, v16
	v_mul_f32_e32 v15, v15, v16
	s_waitcnt vmcnt(0)
	v_lshlrev_b32_e32 v20, 16, v18
	v_and_b32_e32 v21, 0xffff0000, v18
	v_lshlrev_b32_e32 v18, 16, v19
	v_and_b32_e32 v19, 0xffff0000, v19
	v_mul_f32_e32 v14, v14, v18
	v_mul_f32_e32 v15, v15, v19
	v_mul_f32_e32 v12, v12, v20
	v_mul_f32_e32 v13, v13, v21
	s_nop 0
	v_cvt_pk_bf16_f32 v12, v12, v13
	v_cvt_pk_bf16_f32 v13, v14, v15
	global_store_dwordx2 v[24:25], v[12:13], off offset:2560
	v_add_f32_dpp v12, v43, v43 quad_perm:[1,0,3,2] row_mask:0xf bank_mask:0xf bound_ctrl:1
	s_nop 1
	v_add_f32_dpp v12, v12, v12 quad_perm:[2,3,0,1] row_mask:0xf bank_mask:0xf bound_ctrl:1
	s_nop 1
	v_add_f32_dpp v12, v12, v12 row_half_mirror row_mask:0xf bank_mask:0xf bound_ctrl:1
	s_nop 1
	v_add_f32_dpp v12, v12, v12 row_mirror row_mask:0xf bank_mask:0xf bound_ctrl:1
	s_nop 0
	v_readlane_b32 s9, v12, 16
	v_readlane_b32 s10, v12, 48
	v_readlane_b32 s6, v12, 0
	v_readlane_b32 s7, v12, 32
	v_mov_b32_e32 v12, s9
	v_mov_b32_e32 v13, s10
	v_add_f32_e32 v12, s6, v12
	v_add_f32_e32 v13, s7, v13
	s_nop 0
	v_add_f32_e32 v12, v12, v13
	v_fmamk_f32 v12, v12, 0x3b800000, v252
	v_cmp_gt_f32_e32 vcc, s55, v12
	v_mul_f32_e32 v13, 0x4f800000, v12
	s_nop 0
	v_cndmask_b32_e32 v12, v12, v13, vcc
	v_sqrt_f32_e32 v13, v12
	s_nop 0
	v_add_u32_e32 v14, -1, v13
	v_fma_f32 v15, -v14, v13, v12
	v_cmp_ge_f32_e64 s[6:7], 0, v15
	v_add_u32_e32 v15, 1, v13
	s_nop 0
	v_cndmask_b32_e64 v14, v13, v14, s[6:7]
	v_fma_f32 v13, -v15, v13, v12
	v_cmp_lt_f32_e64 s[6:7], 0, v13
	s_nop 1
	v_cndmask_b32_e64 v13, v14, v15, s[6:7]
	v_mul_f32_e32 v14, 0x37800000, v13
	v_cndmask_b32_e32 v13, v13, v14, vcc
	v_cmp_class_f32_e32 vcc, v12, v253
	s_nop 1
	v_cndmask_b32_e32 v12, v13, v12, vcc
	v_div_scale_f32 v13, s[6:7], v12, v12, 1.0
	v_rcp_f32_e32 v14, v13
	s_nop 0
	v_fma_f32 v15, -v13, v14, 1.0
	v_fmac_f32_e32 v14, v15, v14
	v_div_scale_f32 v15, vcc, 1.0, v12, 1.0
	v_mul_f32_e32 v16, v15, v14
	v_fma_f32 v17, -v13, v16, v15
	v_fmac_f32_e32 v16, v17, v14
	v_fma_f32 v13, -v13, v16, v15
	v_div_fmas_f32 v13, v13, v14, v16
	global_load_dwordx2 v[14:15], v[30:31], off offset:3072 nt
	v_div_fixup_f32 v12, v13, v12, 1.0
	v_mul_f32_e32 v8, v8, v12
	v_mul_f32_e32 v9, v9, v12
	v_mul_f32_e32 v10, v10, v12
	v_mul_f32_e32 v11, v11, v12
	s_waitcnt vmcnt(0)
	v_lshlrev_b32_e32 v16, 16, v14
	v_and_b32_e32 v17, 0xffff0000, v14
	v_lshlrev_b32_e32 v14, 16, v15
	v_and_b32_e32 v15, 0xffff0000, v15
	v_mul_f32_e32 v10, v10, v14
	v_mul_f32_e32 v11, v11, v15
	v_mul_f32_e32 v8, v8, v16
	v_mul_f32_e32 v9, v9, v17
	s_nop 0
	v_cvt_pk_bf16_f32 v8, v8, v9
	v_cvt_pk_bf16_f32 v9, v10, v11
	global_store_dwordx2 v[24:25], v[8:9], off offset:3072
	v_add_f32_dpp v8, v42, v42 quad_perm:[1,0,3,2] row_mask:0xf bank_mask:0xf bound_ctrl:1
	s_nop 1
	v_add_f32_dpp v8, v8, v8 quad_perm:[2,3,0,1] row_mask:0xf bank_mask:0xf bound_ctrl:1
	s_nop 1
	v_add_f32_dpp v8, v8, v8 row_half_mirror row_mask:0xf bank_mask:0xf bound_ctrl:1
	s_nop 1
	v_add_f32_dpp v8, v8, v8 row_mirror row_mask:0xf bank_mask:0xf bound_ctrl:1
	s_nop 0
	v_readlane_b32 s9, v8, 16
	v_readlane_b32 s10, v8, 48
	v_readlane_b32 s6, v8, 0
	v_readlane_b32 s7, v8, 32
	v_mov_b32_e32 v8, s9
	v_mov_b32_e32 v9, s10
	v_add_f32_e32 v8, s6, v8
	v_add_f32_e32 v9, s7, v9
	s_nop 0
	v_add_f32_e32 v8, v8, v9
	v_fmamk_f32 v8, v8, 0x3b800000, v252
	v_cmp_gt_f32_e32 vcc, s55, v8
	v_mul_f32_e32 v9, 0x4f800000, v8
	s_nop 0
	v_cndmask_b32_e32 v8, v8, v9, vcc
	v_sqrt_f32_e32 v9, v8
	s_nop 0
	v_add_u32_e32 v10, -1, v9
	v_fma_f32 v11, -v10, v9, v8
	v_cmp_ge_f32_e64 s[6:7], 0, v11
	v_add_u32_e32 v11, 1, v9
	s_nop 0
	v_cndmask_b32_e64 v10, v9, v10, s[6:7]
	v_fma_f32 v9, -v11, v9, v8
	v_cmp_lt_f32_e64 s[6:7], 0, v9
	s_nop 1
	v_cndmask_b32_e64 v9, v10, v11, s[6:7]
	v_mul_f32_e32 v10, 0x37800000, v9
	v_cndmask_b32_e32 v9, v9, v10, vcc
	v_cmp_class_f32_e32 vcc, v8, v253
	s_nop 1
	v_cndmask_b32_e32 v8, v9, v8, vcc
	v_div_scale_f32 v9, s[6:7], v8, v8, 1.0
	v_rcp_f32_e32 v10, v9
	s_nop 0
	v_fma_f32 v11, -v9, v10, 1.0
	v_fmac_f32_e32 v10, v11, v10
	v_div_scale_f32 v11, vcc, 1.0, v8, 1.0
	v_mul_f32_e32 v12, v11, v10
	v_fma_f32 v13, -v9, v12, v11
	v_fmac_f32_e32 v12, v13, v10
	v_fma_f32 v9, -v9, v12, v11
	v_div_fmas_f32 v9, v9, v10, v12
	global_load_dwordx2 v[10:11], v[30:31], off offset:3584 nt
	v_div_fixup_f32 v8, v9, v8, 1.0
	v_mul_f32_e32 v4, v4, v8
	v_mul_f32_e32 v5, v5, v8
	v_mul_f32_e32 v6, v6, v8
	v_mul_f32_e32 v7, v7, v8
	s_waitcnt vmcnt(0)
	v_lshlrev_b32_e32 v12, 16, v10
	v_and_b32_e32 v13, 0xffff0000, v10
	v_lshlrev_b32_e32 v10, 16, v11
	v_and_b32_e32 v11, 0xffff0000, v11
	v_mul_f32_e32 v6, v6, v10
	v_mul_f32_e32 v7, v7, v11
	v_mul_f32_e32 v4, v4, v12
	v_mul_f32_e32 v5, v5, v13
	s_nop 0
	v_cvt_pk_bf16_f32 v4, v4, v5
	v_cvt_pk_bf16_f32 v5, v6, v7
	global_store_dwordx2 v[24:25], v[4:5], off offset:3584
	s_cbranch_scc1 .LBB0_859

; #define LAS __attribute__((address_space(3)))
; __device__ __forceinline__ void relaunder(Frame& F) { int t = mk_tid(); asm volatile("" : "+v"(t)); F.tid = t; F.lane = t & 63; F.wave = __builtin_amdgcn_readfirstlane(t >> 6); }
; template <bool HG>
; __device__ __forceinline__ void readout_phase2(const Args& a, Frame& F, const float* gain, int nrows) {
;     relaunder(F);
;     const int nw = F.vcu * NWAVES + F.wave;
;     const bf16* OF = (const bf16*)(a.ws + WS_OF); const bf16* OB = (const bf16*)(a.ws + WS_OB);
;     const bf16* G = (const bf16*)(a.ws + WS_ACT) + (size_t)(HG ? 6 : 3) * ACT_STRIDE; bf16* HN = (bf16*)(a.ws + WS_HN);
;     LAS float* GL = (LAS float*)F.lds;
;     v2u f0[8], b0[8], g0[8], f1[8], b1[8], g1[8], f2[8], b2[8], g2[8];
;     ...
;     RO_LOAD(f0, b0, g0, nw); RO_LOAD(f1, b1, g1, nw + 2048); RO_LOAD(f2, b2, g2, nw + 2 * 2048);
.LBB0_861:
	s_andn2_b64 vcc, exec, s[6:7]
	s_cbranch_vccnz .LBB0_864
	s_getreg_b32 s6, hwreg(HW_REG_HW_ID, 0, 6)
	s_lshl_b32 s6, s6, 2
	s_add_i32 s6, s6, 0
	s_add_i32 s6, s6, 0x20540
	v_mov_b32_e32 v0, s6
	ds_read_b32 v0, v0
	v_mov_b64_e32 v[2:3], s[0:1]
	s_waitcnt lgkmcnt(0)
	v_readfirstlane_b32 s6, v0
	v_mbcnt_lo_u32_b32 v0, -1, 0
	v_mbcnt_hi_u32_b32 v0, -1, v0
	s_nop 1
	v_lshl_add_u32 v0, s6, 6, v0
	v_mov_b32_e32 v2, s72
	v_mov_b32_e32 v3, s73
	v_readfirstlane_b32 s6, v0
	s_ashr_i32 s6, s6, 6
	s_add_i32 s8, s6, s91
	s_mov_b64 s[6:7], 0x2ac00000
	s_ashr_i32 s9, s8, 31
	v_and_b32_e32 v12, 63, v0
	s_lshl_b64 s[10:11], s[8:9], 12
	v_lshlrev_b32_e32 v0, 3, v12
	s_add_u32 s16, s10, 0x800000
	s_addc_u32 s17, s11, 0
	s_add_u32 s12, s10, 0x1000000
	s_addc_u32 s13, s11, 0
	s_waitcnt vmcnt(0) lgkmcnt(0)
	v_lshl_add_u64 v[4:5], v[2:3], 0, s[6:7]
	s_mov_b64 s[6:7], 0x33400000
	v_lshl_add_u64 v[6:7], v[2:3], 0, s[6:7]
	s_mov_b64 s[6:7], 0x19c00000
	v_lshl_add_u64 v[8:9], v[2:3], 0, s[6:7]
	v_lshl_add_u64 v[10:11], v[4:5], 0, s[10:11]
	v_lshl_add_u64 v[10:11], v[10:11], 0, v[0:1]
	v_lshl_add_u64 v[12:13], v[6:7], 0, s[10:11]
	v_lshl_add_u64 v[14:15], v[8:9], 0, s[10:11]
	v_lshl_add_u64 v[12:13], v[12:13], 0, v[0:1]
	v_lshl_add_u64 v[14:15], v[14:15], 0, v[0:1]
	global_load_dwordx2 v[152:153], v[10:11], off nt
	global_load_dwordx2 v[150:151], v[12:13], off nt
	global_load_dwordx2 v[64:65], v[14:15], off nt
	global_load_dwordx2 v[148:149], v[10:11], off offset:512 nt
	global_load_dwordx2 v[142:143], v[12:13], off offset:512 nt
	global_load_dwordx2 v[58:59], v[14:15], off offset:512 nt
	global_load_dwordx2 v[136:137], v[10:11], off offset:1024 nt
	global_load_dwordx2 v[130:131], v[12:13], off offset:1024 nt
	global_load_dwordx2 v[52:53], v[14:15], off offset:1024 nt
	global_load_dwordx2 v[126:127], v[10:11], off offset:1536 nt
	global_load_dwordx2 v[122:123], v[12:13], off offset:1536 nt
	global_load_dwordx2 v[46:47], v[14:15], off offset:1536 nt
	global_load_dwordx2 v[118:119], v[10:11], off offset:2048 nt
	global_load_dwordx2 v[114:115], v[12:13], off offset:2048 nt
	global_load_dwordx2 v[40:41], v[14:15], off offset:2048 nt
	global_load_dwordx2 v[110:111], v[10:11], off offset:2560 nt
	global_load_dwordx2 v[106:107], v[12:13], off offset:2560 nt
	global_load_dwordx2 v[24:25], v[14:15], off offset:2560 nt
	global_load_dwordx2 v[102:103], v[10:11], off offset:3072 nt
	global_load_dwordx2 v[98:99], v[12:13], off offset:3072 nt
	global_load_dwordx2 v[20:21], v[14:15], off offset:3072 nt
	global_load_dwordx2 v[94:95], v[10:11], off offset:3584 nt
	global_load_dwordx2 v[90:91], v[12:13], off offset:3584 nt
	global_load_dwordx2 v[16:17], v[14:15], off offset:3584 nt
	v_lshl_add_u64 v[10:11], v[4:5], 0, s[16:17]
	v_lshl_add_u64 v[10:11], v[10:11], 0, v[0:1]
	v_lshl_add_u64 v[12:13], v[6:7], 0, s[16:17]
	v_lshl_add_u64 v[14:15], v[8:9], 0, s[16:17]
	v_lshl_add_u64 v[12:13], v[12:13], 0, v[0:1]
	v_lshl_add_u64 v[14:15], v[14:15], 0, v[0:1]
	global_load_dwordx2 v[146:147], v[10:11], off nt
	global_load_dwordx2 v[144:145], v[12:13], off nt
	global_load_dwordx2 v[66:67], v[14:15], off nt
	global_load_dwordx2 v[140:141], v[10:11], off offset:512 nt
	global_load_dwordx2 v[138:139], v[12:13], off offset:512 nt
	global_load_dwordx2 v[60:61], v[14:15], off offset:512 nt
	global_load_dwordx2 v[134:135], v[10:11], off offset:1024 nt
	global_load_dwordx2 v[132:133], v[12:13], off offset:1024 nt
	global_load_dwordx2 v[54:55], v[14:15], off offset:1024 nt
	global_load_dwordx2 v[128:129], v[10:11], off offset:1536 nt
	global_load_dwordx2 v[124:125], v[12:13], off offset:1536 nt
	global_load_dwordx2 v[48:49], v[14:15], off offset:1536 nt
	global_load_dwordx2 v[120:121], v[10:11], off offset:2048 nt
	global_load_dwordx2 v[116:117], v[12:13], off offset:2048 nt
	global_load_dwordx2 v[42:43], v[14:15], off offset:2048 nt
	global_load_dwordx2 v[112:113], v[10:11], off offset:2560 nt
	global_load_dwordx2 v[108:109], v[12:13], off offset:2560 nt
	global_load_dwordx2 v[36:37], v[14:15], off offset:2560 nt
	global_load_dwordx2 v[104:105], v[10:11], off offset:3072 nt
	global_load_dwordx2 v[100:101], v[12:13], off offset:3072 nt
	global_load_dwordx2 v[32:33], v[14:15], off offset:3072 nt
	global_load_dwordx2 v[96:97], v[10:11], off offset:3584 nt
	global_load_dwordx2 v[92:93], v[12:13], off offset:3584 nt
	global_load_dwordx2 v[28:29], v[14:15], off offset:3584 nt
	v_lshl_add_u64 v[10:11], v[4:5], 0, s[12:13]
	v_lshl_add_u64 v[38:39], v[10:11], 0, v[0:1]
	v_lshl_add_u64 v[10:11], v[6:7], 0, s[12:13]
	v_lshl_add_u64 v[12:13], v[8:9], 0, s[12:13]
	v_lshl_add_u64 v[10:11], v[10:11], 0, v[0:1]
	v_lshl_add_u64 v[154:155], v[12:13], 0, v[0:1]
	global_load_dwordx2 v[88:89], v[38:39], off nt
	global_load_dwordx2 v[86:87], v[10:11], off nt
	global_load_dwordx2 v[34:35], v[154:155], off nt
	global_load_dwordx2 v[84:85], v[38:39], off offset:512 nt
	global_load_dwordx2 v[82:83], v[10:11], off offset:512 nt
	global_load_dwordx2 v[30:31], v[154:155], off offset:512 nt
	global_load_dwordx2 v[80:81], v[38:39], off offset:1024 nt
	global_load_dwordx2 v[78:79], v[10:11], off offset:1024 nt
	global_load_dwordx2 v[26:27], v[154:155], off offset:1024 nt
	global_load_dwordx2 v[74:75], v[38:39], off offset:1536 nt
	global_load_dwordx2 v[76:77], v[10:11], off offset:1536 nt
	global_load_dwordx2 v[22:23], v[154:155], off offset:1536 nt
	global_load_dwordx2 v[72:73], v[38:39], off offset:2048 nt
	global_load_dwordx2 v[70:71], v[10:11], off offset:2048 nt
	global_load_dwordx2 v[18:19], v[154:155], off offset:2048 nt
	global_load_dwordx2 v[68:69], v[38:39], off offset:2560 nt
	global_load_dwordx2 v[62:63], v[10:11], off offset:2560 nt
	global_load_dwordx2 v[14:15], v[154:155], off offset:2560 nt
	global_load_dwordx2 v[56:57], v[38:39], off offset:3072 nt
	global_load_dwordx2 v[50:51], v[10:11], off offset:3072 nt
	global_load_dwordx2 v[12:13], v[154:155], off offset:3072 nt
	s_nop 0
	global_load_dwordx2 v[38:39], v[38:39], off offset:3584 nt
	s_nop 0
	global_load_dwordx2 v[44:45], v[10:11], off offset:3584 nt
	s_nop 0
	global_load_dwordx2 v[10:11], v[154:155], off offset:3584 nt
	s_mov_b64 s[6:7], 0x8c00000
	v_lshl_add_u64 v[2:3], v[2:3], 0, s[6:7]
	s_waitcnt vmcnt(62)
	v_lshlrev_b32_e32 v154, 16, v152
	v_and_b32_e32 v155, 0xffff0000, v152
	v_lshlrev_b32_e32 v156, 16, v150
	v_and_b32_e32 v157, 0xffff0000, v150
	v_lshlrev_b32_e32 v152, 16, v153
	v_and_b32_e32 v153, 0xffff0000, v153
	v_lshlrev_b32_e32 v150, 16, v151
	v_and_b32_e32 v151, 0xffff0000, v151
	v_add_f32_e32 v154, v154, v156
	v_add_f32_e32 v155, v155, v157
	v_add_f32_e32 v152, v152, v150
	v_add_f32_e32 v153, v153, v151
	v_mov_b32_e32 v156, v155
	v_mov_b32_e32 v157, v153
	v_mov_b32_e32 v150, v154
	v_mov_b32_e32 v151, v152
	v_mul_f32_e32 v156, v156, v156
	v_mul_f32_e32 v157, v157, v157
	s_waitcnt vmcnt(49)
	v_lshlrev_b32_e32 v162, 16, v90
	v_fma_f32 v150, v150, v150, v156
	v_fma_f32 v151, v151, v151, v157
	v_lshlrev_b32_e32 v156, 16, v142
	v_add_f32_e32 v161, v150, v151
	v_lshlrev_b32_e32 v150, 16, v148
	v_and_b32_e32 v151, 0xffff0000, v148
	v_and_b32_e32 v157, 0xffff0000, v142
	v_lshlrev_b32_e32 v148, 16, v149
	v_and_b32_e32 v149, 0xffff0000, v149
	v_lshlrev_b32_e32 v142, 16, v143
	v_and_b32_e32 v143, 0xffff0000, v143
	v_add_f32_e32 v150, v150, v156
	v_add_f32_e32 v151, v151, v157
	v_add_f32_e32 v148, v148, v142
	v_add_f32_e32 v149, v149, v143
	v_mov_b32_e32 v156, v151
	v_mov_b32_e32 v157, v149
	v_mov_b32_e32 v142, v150
	v_mov_b32_e32 v143, v148
	v_mul_f32_e32 v156, v156, v156
	v_mul_f32_e32 v157, v157, v157
	v_add_f32_dpp v161, v161, v161 quad_perm:[1,0,3,2] row_mask:0xf bank_mask:0xf bound_ctrl:1
	v_fma_f32 v142, v142, v142, v156
	v_fma_f32 v143, v143, v143, v157
	v_lshlrev_b32_e32 v156, 16, v130
	v_add_f32_e32 v166, v142, v143
	v_lshlrev_b32_e32 v142, 16, v136
	v_and_b32_e32 v143, 0xffff0000, v136
	v_and_b32_e32 v157, 0xffff0000, v130
	v_lshlrev_b32_e32 v136, 16, v137
	v_and_b32_e32 v137, 0xffff0000, v137
	v_lshlrev_b32_e32 v130, 16, v131
	v_and_b32_e32 v131, 0xffff0000, v131
	v_add_f32_e32 v142, v142, v156
	v_add_f32_e32 v143, v143, v157
	v_add_f32_e32 v136, v136, v130
	v_add_f32_e32 v137, v137, v131
	v_mov_b32_e32 v156, v143
	v_mov_b32_e32 v157, v137
	v_mov_b32_e32 v130, v142
	v_mov_b32_e32 v131, v136
	v_mul_f32_e32 v156, v156, v156
	v_mul_f32_e32 v157, v157, v157
	v_and_b32_e32 v163, 0xffff0000, v90
	v_fma_f32 v130, v130, v130, v156
	v_fma_f32 v131, v131, v131, v157
	v_lshlrev_b32_e32 v156, 16, v122
	v_add_f32_e32 v160, v130, v131
	v_lshlrev_b32_e32 v130, 16, v126
	v_and_b32_e32 v131, 0xffff0000, v126
	v_and_b32_e32 v157, 0xffff0000, v122
	v_lshlrev_b32_e32 v126, 16, v127
	v_and_b32_e32 v127, 0xffff0000, v127
	v_lshlrev_b32_e32 v122, 16, v123
	v_and_b32_e32 v123, 0xffff0000, v123
	v_add_f32_e32 v130, v130, v156
	v_add_f32_e32 v131, v131, v157
	v_add_f32_e32 v126, v126, v122
	v_add_f32_e32 v127, v127, v123
	v_mov_b32_e32 v156, v131
	v_mov_b32_e32 v157, v127
	v_mov_b32_e32 v122, v130
	v_mov_b32_e32 v123, v126
	v_mul_f32_e32 v156, v156, v156
	v_mul_f32_e32 v157, v157, v157
	v_lshlrev_b32_e32 v90, 16, v91
	v_fma_f32 v122, v122, v122, v156
	v_fma_f32 v123, v123, v123, v157
	v_lshlrev_b32_e32 v156, 16, v114
	v_add_f32_e32 v167, v122, v123
	v_lshlrev_b32_e32 v122, 16, v118
	v_and_b32_e32 v123, 0xffff0000, v118
	v_and_b32_e32 v157, 0xffff0000, v114
	v_lshlrev_b32_e32 v118, 16, v119
	v_and_b32_e32 v119, 0xffff0000, v119
	v_lshlrev_b32_e32 v114, 16, v115
	v_and_b32_e32 v115, 0xffff0000, v115
	v_add_f32_e32 v122, v122, v156
	v_add_f32_e32 v123, v123, v157
	v_add_f32_e32 v118, v118, v114
	v_add_f32_e32 v119, v119, v115
	v_mov_b32_e32 v156, v123
	v_mov_b32_e32 v157, v119
	v_mov_b32_e32 v114, v122
	v_mov_b32_e32 v115, v118
	v_mul_f32_e32 v156, v156, v156
	v_mul_f32_e32 v157, v157, v157
	v_and_b32_e32 v91, 0xffff0000, v91
	v_fma_f32 v114, v114, v114, v156
	v_fma_f32 v115, v115, v115, v157
	v_lshlrev_b32_e32 v156, 16, v106
	v_add_f32_e32 v159, v114, v115
	v_lshlrev_b32_e32 v114, 16, v110
	v_and_b32_e32 v115, 0xffff0000, v110
	v_and_b32_e32 v157, 0xffff0000, v106
	v_lshlrev_b32_e32 v110, 16, v111
	v_and_b32_e32 v111, 0xffff0000, v111
	v_lshlrev_b32_e32 v106, 16, v107
	v_and_b32_e32 v107, 0xffff0000, v107
	v_add_f32_e32 v114, v114, v156
	v_add_f32_e32 v115, v115, v157
	v_add_f32_e32 v110, v110, v106
	v_add_f32_e32 v111, v111, v107
	v_mov_b32_e32 v156, v115
	v_mov_b32_e32 v157, v111
	v_mov_b32_e32 v106, v114
	v_mov_b32_e32 v107, v110
	v_mul_f32_e32 v156, v156, v156
	v_mul_f32_e32 v157, v157, v157
	v_add_f32_dpp v161, v161, v161 quad_perm:[2,3,0,1] row_mask:0xf bank_mask:0xf bound_ctrl:1
	v_fma_f32 v106, v106, v106, v156
	v_fma_f32 v107, v107, v107, v157
	v_lshlrev_b32_e32 v156, 16, v98
	v_add_f32_e32 v158, v106, v107
	v_lshlrev_b32_e32 v106, 16, v102
	v_and_b32_e32 v107, 0xffff0000, v102
	v_and_b32_e32 v157, 0xffff0000, v98
	v_lshlrev_b32_e32 v102, 16, v103
	v_and_b32_e32 v103, 0xffff0000, v103
	v_lshlrev_b32_e32 v98, 16, v99
	v_and_b32_e32 v99, 0xffff0000, v99
	v_add_f32_e32 v106, v106, v156
	v_add_f32_e32 v107, v107, v157
	v_add_f32_e32 v102, v102, v98
	v_add_f32_e32 v103, v103, v99
	v_mov_b32_e32 v156, v107
	v_mov_b32_e32 v157, v103
	v_mov_b32_e32 v98, v106
	v_mov_b32_e32 v99, v102
	v_mul_f32_e32 v156, v156, v156
	v_mul_f32_e32 v157, v157, v157
	v_add_f32_dpp v161, v161, v161 row_half_mirror row_mask:0xf bank_mask:0xf bound_ctrl:1
	v_fma_f32 v98, v98, v98, v156
	v_fma_f32 v99, v99, v99, v157
	s_nop 0
	v_add_f32_e32 v157, v98, v99
	v_lshlrev_b32_e32 v98, 16, v94
	v_and_b32_e32 v99, 0xffff0000, v94
	v_lshlrev_b32_e32 v94, 16, v95
	v_and_b32_e32 v95, 0xffff0000, v95
	v_add_f32_e32 v98, v98, v162
	v_add_f32_e32 v99, v99, v163
	v_add_f32_e32 v90, v94, v90
	v_add_f32_e32 v91, v95, v91
	v_mov_b32_e32 v162, v99
	v_mov_b32_e32 v163, v91
	v_add_f32_dpp v161, v161, v161 row_mirror row_mask:0xf bank_mask:0xf bound_ctrl:1
	v_mov_b32_e32 v94, v98
	v_mov_b32_e32 v95, v90
	v_mul_f32_e32 v162, v162, v162
	v_mul_f32_e32 v163, v163, v163
	v_readlane_b32 s9, v161, 16
	v_readlane_b32 s14, v161, 48
	v_fma_f32 v94, v94, v94, v162
	v_fma_f32 v95, v95, v95, v163
	v_readlane_b32 s6, v161, 0
	v_readlane_b32 s7, v161, 32
	v_mov_b32_e32 v162, s9
	v_mov_b32_e32 v163, s14
	v_add_f32_e32 v162, s6, v162
	v_add_f32_e32 v163, s7, v163
	v_add_f32_e32 v156, v94, v95
	v_add_f32_e32 v161, v162, v163
	v_fmamk_f32 v161, v161, 0x3b800000, v252
	v_cmp_gt_f32_e32 vcc, s55, v161
	v_mul_f32_e32 v162, 0x4f800000, v161
	v_lshl_add_u64 v[94:95], v[2:3], 0, s[10:11]
	v_cndmask_b32_e32 v161, v161, v162, vcc
	v_sqrt_f32_e32 v162, v161
	v_lshl_add_u64 v[94:95], v[94:95], 0, v[0:1]
	v_add_u32_e32 v163, -1, v162
	v_fma_f32 v164, -v163, v162, v161
	v_cmp_ge_f32_e64 s[6:7], 0, v164
	v_add_u32_e32 v164, 1, v162
	s_nop 0
	v_cndmask_b32_e64 v163, v162, v163, s[6:7]
	v_fma_f32 v162, -v164, v162, v161
	v_cmp_lt_f32_e64 s[6:7], 0, v162
	s_nop 1
	v_cndmask_b32_e64 v162, v163, v164, s[6:7]
	v_mul_f32_e32 v163, 0x37800000, v162
	v_cndmask_b32_e32 v162, v162, v163, vcc
	v_cmp_class_f32_e32 vcc, v161, v253
	s_nop 1
	v_cndmask_b32_e32 v161, v162, v161, vcc
	v_div_scale_f32 v162, s[6:7], v161, v161, 1.0
	v_rcp_f32_e32 v163, v162
	s_nop 0
	v_fma_f32 v164, -v162, v163, 1.0
	v_fmac_f32_e32 v163, v164, v163
	v_div_scale_f32 v164, vcc, 1.0, v161, 1.0
	v_mul_f32_e32 v165, v164, v163
	v_fma_f32 v168, -v162, v165, v164
	v_fmac_f32_e32 v165, v168, v163
	v_fma_f32 v162, -v162, v165, v164
	v_div_fmas_f32 v162, v162, v163, v165
	v_div_fixup_f32 v162, v162, v161, 1.0
	v_lshlrev_b32_e32 v164, 16, v64
	v_and_b32_e32 v165, 0xffff0000, v64
	v_lshlrev_b32_e32 v64, 16, v65
	v_and_b32_e32 v65, 0xffff0000, v65
	v_mul_f32_e32 v154, v154, v162
	v_mul_f32_e32 v155, v155, v162
	v_mul_f32_e32 v152, v152, v162
	v_mul_f32_e32 v153, v153, v162
	s_nop 0
	v_mul_f32_e32 v64, v152, v64
	v_mul_f32_e32 v65, v153, v65
	v_mul_f32_e32 v152, v154, v164
	v_mul_f32_e32 v153, v155, v165
	s_nop 0
	v_cvt_pk_bf16_f32 v152, v152, v153
	v_cvt_pk_bf16_f32 v153, v64, v65
	v_add_f32_dpp v64, v166, v166 quad_perm:[1,0,3,2] row_mask:0xf bank_mask:0xf bound_ctrl:1
	global_store_dwordx2 v[94:95], v[152:153], off
	s_nop 0
	v_add_f32_dpp v64, v64, v64 quad_perm:[2,3,0,1] row_mask:0xf bank_mask:0xf bound_ctrl:1
	s_nop 1
	v_add_f32_dpp v64, v64, v64 row_half_mirror row_mask:0xf bank_mask:0xf bound_ctrl:1
	s_nop 1
	v_add_f32_dpp v64, v64, v64 row_mirror row_mask:0xf bank_mask:0xf bound_ctrl:1
	s_nop 0
	v_readlane_b32 s9, v64, 16
	v_readlane_b32 s14, v64, 48
	v_readlane_b32 s6, v64, 0
	v_readlane_b32 s7, v64, 32
	v_mov_b32_e32 v64, s9
	v_mov_b32_e32 v65, s14
	v_add_f32_e32 v64, s6, v64
	v_add_f32_e32 v65, s7, v65
	s_nop 0
	v_add_f32_e32 v64, v64, v65
	v_fmamk_f32 v64, v64, 0x3b800000, v252
	v_cmp_gt_f32_e32 vcc, s55, v64
	v_mul_f32_e32 v65, 0x4f800000, v64
	s_nop 0
	v_cndmask_b32_e32 v64, v64, v65, vcc
	v_sqrt_f32_e32 v65, v64
	s_nop 0
	v_add_u32_e32 v152, -1, v65
	v_fma_f32 v153, -v152, v65, v64
	v_cmp_ge_f32_e64 s[6:7], 0, v153
	v_add_u32_e32 v153, 1, v65
	s_nop 0
	v_cndmask_b32_e64 v152, v65, v152, s[6:7]
	v_fma_f32 v65, -v153, v65, v64
	v_cmp_lt_f32_e64 s[6:7], 0, v65
	s_nop 1
	v_cndmask_b32_e64 v65, v152, v153, s[6:7]
	v_mul_f32_e32 v152, 0x37800000, v65
	v_cndmask_b32_e32 v65, v65, v152, vcc
	v_cmp_class_f32_e32 vcc, v64, v253
	s_nop 1
	v_cndmask_b32_e32 v64, v65, v64, vcc
	v_div_scale_f32 v65, s[6:7], v64, v64, 1.0
	v_rcp_f32_e32 v152, v65
	s_nop 0
	v_fma_f32 v153, -v65, v152, 1.0
	v_fmac_f32_e32 v152, v153, v152
	v_div_scale_f32 v153, vcc, 1.0, v64, 1.0
	v_mul_f32_e32 v154, v153, v152
	v_fma_f32 v155, -v65, v154, v153
	v_fmac_f32_e32 v154, v155, v152
	v_fma_f32 v65, -v65, v154, v153
	v_div_fmas_f32 v65, v65, v152, v154
	v_div_fixup_f32 v64, v65, v64, 1.0
	v_lshlrev_b32_e32 v152, 16, v58
	v_and_b32_e32 v153, 0xffff0000, v58
	v_lshlrev_b32_e32 v58, 16, v59
	v_and_b32_e32 v59, 0xffff0000, v59
	v_mul_f32_e32 v150, v150, v64
	v_mul_f32_e32 v151, v151, v64
	v_mul_f32_e32 v65, v149, v64
	v_mul_f32_e32 v64, v148, v64
	s_nop 0
	v_mul_f32_e32 v58, v64, v58
	v_mul_f32_e32 v59, v65, v59
	v_mul_f32_e32 v64, v150, v152
	v_mul_f32_e32 v65, v151, v153
	s_waitcnt vmcnt(47)
	v_lshlrev_b32_e32 v152, 16, v144
	v_cvt_pk_bf16_f32 v64, v64, v65
	v_cvt_pk_bf16_f32 v65, v58, v59
	v_add_f32_dpp v58, v160, v160 quad_perm:[1,0,3,2] row_mask:0xf bank_mask:0xf bound_ctrl:1
	global_store_dwordx2 v[94:95], v[64:65], off offset:512
	v_and_b32_e32 v153, 0xffff0000, v144
	v_add_f32_dpp v58, v58, v58 quad_perm:[2,3,0,1] row_mask:0xf bank_mask:0xf bound_ctrl:1
	v_lshlrev_b32_e32 v144, 16, v145
	v_and_b32_e32 v145, 0xffff0000, v145
	v_add_f32_dpp v58, v58, v58 row_half_mirror row_mask:0xf bank_mask:0xf bound_ctrl:1
	s_nop 1
	v_add_f32_dpp v58, v58, v58 row_mirror row_mask:0xf bank_mask:0xf bound_ctrl:1
	s_nop 0
	v_readlane_b32 s9, v58, 16
	v_readlane_b32 s14, v58, 48
	v_readlane_b32 s6, v58, 0
	v_readlane_b32 s7, v58, 32
	v_mov_b32_e32 v58, s9
	v_mov_b32_e32 v59, s14
	v_add_f32_e32 v58, s6, v58
	v_add_f32_e32 v59, s7, v59
	s_nop 0
	v_add_f32_e32 v58, v58, v59
	v_fmamk_f32 v58, v58, 0x3b800000, v252
	v_cmp_gt_f32_e32 vcc, s55, v58
	v_mul_f32_e32 v59, 0x4f800000, v58
	s_nop 0
	v_cndmask_b32_e32 v58, v58, v59, vcc
	v_sqrt_f32_e32 v59, v58
	s_nop 0
	v_add_u32_e32 v64, -1, v59
	v_fma_f32 v65, -v64, v59, v58
	v_cmp_ge_f32_e64 s[6:7], 0, v65
	v_add_u32_e32 v65, 1, v59
	s_nop 0
	v_cndmask_b32_e64 v64, v59, v64, s[6:7]
	v_fma_f32 v59, -v65, v59, v58
	v_cmp_lt_f32_e64 s[6:7], 0, v59
	s_nop 1
	v_cndmask_b32_e64 v59, v64, v65, s[6:7]
	v_mul_f32_e32 v64, 0x37800000, v59
	v_cndmask_b32_e32 v59, v59, v64, vcc
	v_cmp_class_f32_e32 vcc, v58, v253
	s_nop 1
	v_cndmask_b32_e32 v58, v59, v58, vcc
	v_div_scale_f32 v59, s[6:7], v58, v58, 1.0
	v_rcp_f32_e32 v64, v59
	s_nop 0
	v_fma_f32 v65, -v59, v64, 1.0
	v_fmac_f32_e32 v64, v65, v64
	v_div_scale_f32 v65, vcc, 1.0, v58, 1.0
	v_mul_f32_e32 v148, v65, v64
	v_fma_f32 v149, -v59, v148, v65
	v_fmac_f32_e32 v148, v149, v64
	v_fma_f32 v59, -v59, v148, v65
	v_div_fmas_f32 v59, v59, v64, v148
	v_div_fixup_f32 v58, v59, v58, 1.0
	v_lshlrev_b32_e32 v64, 16, v52
	v_and_b32_e32 v65, 0xffff0000, v52
	v_lshlrev_b32_e32 v52, 16, v53
	v_and_b32_e32 v53, 0xffff0000, v53
	v_mul_f32_e32 v142, v142, v58
	v_mul_f32_e32 v143, v143, v58
	v_mul_f32_e32 v59, v137, v58
	v_mul_f32_e32 v58, v136, v58
	s_nop 0
	v_mul_f32_e32 v52, v58, v52
	v_mul_f32_e32 v53, v59, v53
	v_mul_f32_e32 v58, v142, v64
	v_mul_f32_e32 v59, v143, v65
	s_nop 0
	v_cvt_pk_bf16_f32 v58, v58, v59
	v_cvt_pk_bf16_f32 v59, v52, v53
	v_add_f32_dpp v52, v167, v167 quad_perm:[1,0,3,2] row_mask:0xf bank_mask:0xf bound_ctrl:1
	global_store_dwordx2 v[94:95], v[58:59], off offset:1024
	s_nop 0
	v_add_f32_dpp v52, v52, v52 quad_perm:[2,3,0,1] row_mask:0xf bank_mask:0xf bound_ctrl:1
	s_nop 1
	v_add_f32_dpp v52, v52, v52 row_half_mirror row_mask:0xf bank_mask:0xf bound_ctrl:1
	s_nop 1
	v_add_f32_dpp v52, v52, v52 row_mirror row_mask:0xf bank_mask:0xf bound_ctrl:1
	s_nop 0
	v_readlane_b32 s9, v52, 16
	v_readlane_b32 s14, v52, 48
	v_readlane_b32 s6, v52, 0
	v_readlane_b32 s7, v52, 32
	v_mov_b32_e32 v52, s9
	v_mov_b32_e32 v53, s14
	v_add_f32_e32 v52, s6, v52
	v_add_f32_e32 v53, s7, v53
	s_nop 0
	v_add_f32_e32 v52, v52, v53
	v_fmamk_f32 v52, v52, 0x3b800000, v252
	v_cmp_gt_f32_e32 vcc, s55, v52
	v_mul_f32_e32 v53, 0x4f800000, v52
	s_nop 0
	v_cndmask_b32_e32 v52, v52, v53, vcc
	v_sqrt_f32_e32 v53, v52
	s_nop 0
	v_add_u32_e32 v58, -1, v53
	v_fma_f32 v59, -v58, v53, v52
	v_cmp_ge_f32_e64 s[6:7], 0, v59
	v_add_u32_e32 v59, 1, v53
	s_nop 0
	v_cndmask_b32_e64 v58, v53, v58, s[6:7]
	v_fma_f32 v53, -v59, v53, v52
	v_cmp_lt_f32_e64 s[6:7], 0, v53
	s_nop 1
	v_cndmask_b32_e64 v53, v58, v59, s[6:7]
	v_mul_f32_e32 v58, 0x37800000, v53
	v_cndmask_b32_e32 v53, v53, v58, vcc
	v_cmp_class_f32_e32 vcc, v52, v253
	s_nop 1
	v_cndmask_b32_e32 v52, v53, v52, vcc
	v_div_scale_f32 v53, s[6:7], v52, v52, 1.0
	v_rcp_f32_e32 v58, v53
	s_nop 0
	v_fma_f32 v59, -v53, v58, 1.0
	v_fmac_f32_e32 v58, v59, v58
	v_div_scale_f32 v59, vcc, 1.0, v52, 1.0
	v_mul_f32_e32 v64, v59, v58
	v_fma_f32 v65, -v53, v64, v59
	v_fmac_f32_e32 v64, v65, v58
	v_fma_f32 v53, -v53, v64, v59
	v_div_fmas_f32 v53, v53, v58, v64
	v_div_fixup_f32 v52, v53, v52, 1.0
	v_lshlrev_b32_e32 v58, 16, v46
	v_and_b32_e32 v59, 0xffff0000, v46
	v_lshlrev_b32_e32 v46, 16, v47
	v_and_b32_e32 v47, 0xffff0000, v47
	v_mul_f32_e32 v64, v130, v52
	v_mul_f32_e32 v65, v131, v52
	v_mul_f32_e32 v53, v127, v52
	v_mul_f32_e32 v52, v126, v52
	s_nop 0
	v_mul_f32_e32 v46, v52, v46
	v_mul_f32_e32 v47, v53, v47
	v_mul_f32_e32 v52, v64, v58
	v_mul_f32_e32 v53, v65, v59
	s_nop 0
	v_cvt_pk_bf16_f32 v52, v52, v53
	v_cvt_pk_bf16_f32 v53, v46, v47
	v_add_f32_dpp v46, v159, v159 quad_perm:[1,0,3,2] row_mask:0xf bank_mask:0xf bound_ctrl:1
	global_store_dwordx2 v[94:95], v[52:53], off offset:1536
	s_waitcnt vmcnt(29)
	v_and_b32_e32 v159, 0xffff0000, v92
	v_add_f32_dpp v46, v46, v46 quad_perm:[2,3,0,1] row_mask:0xf bank_mask:0xf bound_ctrl:1
	s_nop 1
	v_add_f32_dpp v46, v46, v46 row_half_mirror row_mask:0xf bank_mask:0xf bound_ctrl:1
	s_nop 1
	v_add_f32_dpp v46, v46, v46 row_mirror row_mask:0xf bank_mask:0xf bound_ctrl:1
	s_nop 0
	v_readlane_b32 s9, v46, 16
	v_readlane_b32 s14, v46, 48
	v_readlane_b32 s6, v46, 0
	v_readlane_b32 s7, v46, 32
	v_mov_b32_e32 v46, s9
	v_mov_b32_e32 v47, s14
	v_add_f32_e32 v46, s6, v46
	v_add_f32_e32 v47, s7, v47
	s_nop 0
	v_add_f32_e32 v46, v46, v47
	v_fmamk_f32 v46, v46, 0x3b800000, v252
	v_cmp_gt_f32_e32 vcc, s55, v46
	v_mul_f32_e32 v47, 0x4f800000, v46
	s_nop 0
	v_cndmask_b32_e32 v46, v46, v47, vcc
	v_sqrt_f32_e32 v47, v46
	s_nop 0
	v_add_u32_e32 v52, -1, v47
	v_fma_f32 v53, -v52, v47, v46
	v_cmp_ge_f32_e64 s[6:7], 0, v53
	v_add_u32_e32 v53, 1, v47
	s_nop 0
	v_cndmask_b32_e64 v52, v47, v52, s[6:7]
	v_fma_f32 v47, -v53, v47, v46
	v_cmp_lt_f32_e64 s[6:7], 0, v47
	s_nop 1
	v_cndmask_b32_e64 v47, v52, v53, s[6:7]
	v_mul_f32_e32 v52, 0x37800000, v47
	v_cndmask_b32_e32 v47, v47, v52, vcc
	v_cmp_class_f32_e32 vcc, v46, v253
	s_nop 1
	v_cndmask_b32_e32 v46, v47, v46, vcc
	v_div_scale_f32 v47, s[6:7], v46, v46, 1.0
	v_rcp_f32_e32 v52, v47
	s_nop 0
	v_fma_f32 v53, -v47, v52, 1.0
	v_fmac_f32_e32 v52, v53, v52
	v_div_scale_f32 v53, vcc, 1.0, v46, 1.0
	v_mul_f32_e32 v58, v53, v52
	v_fma_f32 v59, -v47, v58, v53
	v_fmac_f32_e32 v58, v59, v52
	v_fma_f32 v47, -v47, v58, v53
	v_div_fmas_f32 v47, v47, v52, v58
	v_div_fixup_f32 v46, v47, v46, 1.0
	v_lshlrev_b32_e32 v52, 16, v40
	v_and_b32_e32 v53, 0xffff0000, v40
	v_lshlrev_b32_e32 v40, 16, v41
	v_and_b32_e32 v41, 0xffff0000, v41
	v_mul_f32_e32 v58, v122, v46
	v_mul_f32_e32 v59, v123, v46
	v_mul_f32_e32 v47, v119, v46
	v_mul_f32_e32 v46, v118, v46
	s_nop 0
	v_mul_f32_e32 v40, v46, v40
	v_mul_f32_e32 v41, v47, v41
	v_mul_f32_e32 v46, v58, v52
	v_mul_f32_e32 v47, v59, v53
	s_nop 0
	v_cvt_pk_bf16_f32 v46, v46, v47
	v_cvt_pk_bf16_f32 v47, v40, v41
	v_add_f32_dpp v40, v158, v158 quad_perm:[1,0,3,2] row_mask:0xf bank_mask:0xf bound_ctrl:1
	global_store_dwordx2 v[94:95], v[46:47], off offset:2048
	v_lshlrev_b32_e32 v158, 16, v92
	v_add_f32_dpp v40, v40, v40 quad_perm:[2,3,0,1] row_mask:0xf bank_mask:0xf bound_ctrl:1
	v_lshlrev_b32_e32 v92, 16, v93
	v_and_b32_e32 v93, 0xffff0000, v93
	v_add_f32_dpp v40, v40, v40 row_half_mirror row_mask:0xf bank_mask:0xf bound_ctrl:1
	s_nop 1
	v_add_f32_dpp v40, v40, v40 row_mirror row_mask:0xf bank_mask:0xf bound_ctrl:1
	s_nop 0
	v_readlane_b32 s9, v40, 16
	v_readlane_b32 s14, v40, 48
	v_readlane_b32 s6, v40, 0
	v_readlane_b32 s7, v40, 32
	v_mov_b32_e32 v40, s9
	v_mov_b32_e32 v41, s14
	v_add_f32_e32 v40, s6, v40
	v_add_f32_e32 v41, s7, v41
	s_nop 0
	v_add_f32_e32 v40, v40, v41
	v_fmamk_f32 v40, v40, 0x3b800000, v252
	v_cmp_gt_f32_e32 vcc, s55, v40
	v_mul_f32_e32 v41, 0x4f800000, v40
	s_nop 0
	v_cndmask_b32_e32 v40, v40, v41, vcc
	v_sqrt_f32_e32 v41, v40
	s_nop 0
	v_add_u32_e32 v46, -1, v41
	v_fma_f32 v47, -v46, v41, v40
	v_cmp_ge_f32_e64 s[6:7], 0, v47
	v_add_u32_e32 v47, 1, v41
	s_nop 0
	v_cndmask_b32_e64 v46, v41, v46, s[6:7]
	v_fma_f32 v41, -v47, v41, v40
	v_cmp_lt_f32_e64 s[6:7], 0, v41
	s_nop 1
	v_cndmask_b32_e64 v41, v46, v47, s[6:7]
	v_mul_f32_e32 v46, 0x37800000, v41
	v_cndmask_b32_e32 v41, v41, v46, vcc
	v_cmp_class_f32_e32 vcc, v40, v253
	s_nop 1
	v_cndmask_b32_e32 v40, v41, v40, vcc
	v_div_scale_f32 v41, s[6:7], v40, v40, 1.0
	v_rcp_f32_e32 v46, v41
	s_nop 0
	v_fma_f32 v47, -v41, v46, 1.0
	v_fmac_f32_e32 v46, v47, v46
	v_div_scale_f32 v47, vcc, 1.0, v40, 1.0
	v_mul_f32_e32 v52, v47, v46
	v_fma_f32 v53, -v41, v52, v47
	v_fmac_f32_e32 v52, v53, v46
	v_fma_f32 v41, -v41, v52, v47
	v_div_fmas_f32 v41, v41, v46, v52
	v_div_fixup_f32 v40, v41, v40, 1.0
	v_lshlrev_b32_e32 v46, 16, v24
	v_and_b32_e32 v47, 0xffff0000, v24
	v_lshlrev_b32_e32 v24, 16, v25
	v_and_b32_e32 v25, 0xffff0000, v25
	v_mul_f32_e32 v52, v114, v40
	v_mul_f32_e32 v53, v115, v40
	v_mul_f32_e32 v41, v111, v40
	v_mul_f32_e32 v40, v110, v40
	s_nop 0
	v_mul_f32_e32 v24, v40, v24
	v_mul_f32_e32 v25, v41, v25
	v_mul_f32_e32 v40, v52, v46
	v_mul_f32_e32 v41, v53, v47
	s_nop 0
	v_cvt_pk_bf16_f32 v40, v40, v41
	v_cvt_pk_bf16_f32 v41, v24, v25
	v_add_f32_dpp v24, v157, v157 quad_perm:[1,0,3,2] row_mask:0xf bank_mask:0xf bound_ctrl:1
	global_store_dwordx2 v[94:95], v[40:41], off offset:2560
	s_nop 0
	v_add_f32_dpp v24, v24, v24 quad_perm:[2,3,0,1] row_mask:0xf bank_mask:0xf bound_ctrl:1
	s_nop 1
	v_add_f32_dpp v24, v24, v24 row_half_mirror row_mask:0xf bank_mask:0xf bound_ctrl:1
	s_nop 1
	v_add_f32_dpp v24, v24, v24 row_mirror row_mask:0xf bank_mask:0xf bound_ctrl:1
	s_nop 0
	v_readlane_b32 s9, v24, 16
	v_readlane_b32 s14, v24, 48
	v_readlane_b32 s6, v24, 0
	v_readlane_b32 s7, v24, 32
	v_mov_b32_e32 v24, s9
	v_mov_b32_e32 v25, s14
	v_add_f32_e32 v24, s6, v24
	v_add_f32_e32 v25, s7, v25
	s_nop 0
	v_add_f32_e32 v24, v24, v25
	v_fmamk_f32 v24, v24, 0x3b800000, v252
	v_cmp_gt_f32_e32 vcc, s55, v24
	v_mul_f32_e32 v25, 0x4f800000, v24
	s_nop 0
	v_cndmask_b32_e32 v24, v24, v25, vcc
	v_sqrt_f32_e32 v25, v24
	s_nop 0
	v_add_u32_e32 v40, -1, v25
	v_fma_f32 v41, -v40, v25, v24
	v_cmp_ge_f32_e64 s[6:7], 0, v41
	v_add_u32_e32 v41, 1, v25
	s_nop 0
	v_cndmask_b32_e64 v40, v25, v40, s[6:7]
	v_fma_f32 v25, -v41, v25, v24
	v_cmp_lt_f32_e64 s[6:7], 0, v25
	s_nop 1
	v_cndmask_b32_e64 v25, v40, v41, s[6:7]
	v_mul_f32_e32 v40, 0x37800000, v25
	v_cndmask_b32_e32 v25, v25, v40, vcc
	v_cmp_class_f32_e32 vcc, v24, v253
	s_nop 1
	v_cndmask_b32_e32 v24, v25, v24, vcc
	v_div_scale_f32 v25, s[6:7], v24, v24, 1.0
	v_rcp_f32_e32 v40, v25
	s_nop 0
	v_fma_f32 v41, -v25, v40, 1.0
	v_fmac_f32_e32 v40, v41, v40
	v_div_scale_f32 v41, vcc, 1.0, v24, 1.0
	v_mul_f32_e32 v46, v41, v40
	v_fma_f32 v47, -v25, v46, v41
	v_fmac_f32_e32 v46, v47, v40
	v_fma_f32 v25, -v25, v46, v41
	v_div_fmas_f32 v25, v25, v40, v46
	v_div_fixup_f32 v24, v25, v24, 1.0
	v_lshlrev_b32_e32 v40, 16, v20
	v_and_b32_e32 v41, 0xffff0000, v20
	v_lshlrev_b32_e32 v20, 16, v21
	v_and_b32_e32 v21, 0xffff0000, v21
	v_mul_f32_e32 v46, v106, v24
	v_mul_f32_e32 v47, v107, v24
	v_mul_f32_e32 v25, v103, v24
	v_mul_f32_e32 v24, v102, v24
	s_nop 0
	v_mul_f32_e32 v20, v24, v20
	v_mul_f32_e32 v21, v25, v21
	v_mul_f32_e32 v24, v46, v40
	v_mul_f32_e32 v25, v47, v41
	s_nop 0
	v_cvt_pk_bf16_f32 v24, v24, v25
	v_cvt_pk_bf16_f32 v25, v20, v21
	v_add_f32_dpp v20, v156, v156 quad_perm:[1,0,3,2] row_mask:0xf bank_mask:0xf bound_ctrl:1
	global_store_dwordx2 v[94:95], v[24:25], off offset:3072
	s_nop 0
	v_add_f32_dpp v20, v20, v20 quad_perm:[2,3,0,1] row_mask:0xf bank_mask:0xf bound_ctrl:1
	s_nop 1
	v_add_f32_dpp v20, v20, v20 row_half_mirror row_mask:0xf bank_mask:0xf bound_ctrl:1
	s_nop 1
	v_add_f32_dpp v20, v20, v20 row_mirror row_mask:0xf bank_mask:0xf bound_ctrl:1
	s_nop 0
	v_readlane_b32 s9, v20, 16
	v_readlane_b32 s14, v20, 48
	v_readlane_b32 s6, v20, 0
	v_readlane_b32 s7, v20, 32
	v_mov_b32_e32 v20, s9
	v_mov_b32_e32 v21, s14
	v_add_f32_e32 v20, s6, v20
	v_add_f32_e32 v21, s7, v21
	s_add_u32 s14, s10, 0x1800000
	v_add_f32_e32 v20, v20, v21
	v_fmamk_f32 v20, v20, 0x3b800000, v252
	v_cmp_gt_f32_e32 vcc, s55, v20
	v_mul_f32_e32 v21, 0x4f800000, v20
	s_addc_u32 s15, s11, 0
	v_cndmask_b32_e32 v20, v20, v21, vcc
	v_sqrt_f32_e32 v21, v20
	s_nop 0
	v_add_u32_e32 v24, -1, v21
	v_fma_f32 v25, -v24, v21, v20
	v_cmp_ge_f32_e64 s[6:7], 0, v25
	v_add_u32_e32 v25, 1, v21
	s_nop 0
	v_cndmask_b32_e64 v24, v21, v24, s[6:7]
	v_fma_f32 v21, -v25, v21, v20
	v_cmp_lt_f32_e64 s[6:7], 0, v21
	s_nop 1
	v_cndmask_b32_e64 v21, v24, v25, s[6:7]
	v_mul_f32_e32 v24, 0x37800000, v21
	v_cndmask_b32_e32 v21, v21, v24, vcc
	v_cmp_class_f32_e32 vcc, v20, v253
	s_nop 1
	v_cndmask_b32_e32 v20, v21, v20, vcc
	v_div_scale_f32 v21, s[6:7], v20, v20, 1.0
	v_rcp_f32_e32 v24, v21
	s_nop 0
	v_fma_f32 v25, -v21, v24, 1.0
	v_fmac_f32_e32 v24, v25, v24
	v_div_scale_f32 v25, vcc, 1.0, v20, 1.0
	v_mul_f32_e32 v40, v25, v24
	v_fma_f32 v41, -v21, v40, v25
	v_fmac_f32_e32 v40, v41, v24
	v_fma_f32 v21, -v21, v40, v25
	v_div_fmas_f32 v21, v21, v24, v40
	v_div_fixup_f32 v20, v21, v20, 1.0
	v_lshlrev_b32_e32 v24, 16, v16
	v_and_b32_e32 v25, 0xffff0000, v16
	v_lshlrev_b32_e32 v16, 16, v17
	v_and_b32_e32 v17, 0xffff0000, v17
	v_mul_f32_e32 v40, v98, v20
	v_mul_f32_e32 v41, v99, v20
	v_mul_f32_e32 v21, v91, v20
	v_mul_f32_e32 v20, v90, v20
	s_nop 0
	v_mul_f32_e32 v16, v20, v16
	v_mul_f32_e32 v17, v21, v17
	v_mul_f32_e32 v20, v40, v24
	v_mul_f32_e32 v21, v41, v25
	s_nop 0
	v_cvt_pk_bf16_f32 v20, v20, v21
	v_cvt_pk_bf16_f32 v21, v16, v17
	global_store_dwordx2 v[94:95], v[20:21], off offset:3584
	v_lshl_add_u64 v[20:21], v[6:7], 0, s[14:15]
	v_lshl_add_u64 v[16:17], v[4:5], 0, s[14:15]
	v_lshl_add_u64 v[94:95], v[20:21], 0, v[0:1]
	v_lshl_add_u64 v[20:21], v[8:9], 0, s[14:15]
	v_lshl_add_u64 v[16:17], v[16:17], 0, v[0:1]
	v_lshl_add_u64 v[150:151], v[20:21], 0, v[0:1]
	global_load_dwordx2 v[160:161], v[16:17], off nt
	global_load_dwordx2 v[154:155], v[94:95], off nt
	global_load_dwordx2 v[64:65], v[150:151], off nt
	global_load_dwordx2 v[148:149], v[16:17], off offset:512 nt
	global_load_dwordx2 v[142:143], v[94:95], off offset:512 nt
	global_load_dwordx2 v[58:59], v[150:151], off offset:512 nt
	global_load_dwordx2 v[136:137], v[16:17], off offset:1024 nt
	global_load_dwordx2 v[130:131], v[94:95], off offset:1024 nt
	global_load_dwordx2 v[52:53], v[150:151], off offset:1024 nt
	global_load_dwordx2 v[122:123], v[16:17], off offset:1536 nt
	global_load_dwordx2 v[126:127], v[94:95], off offset:1536 nt
	global_load_dwordx2 v[46:47], v[150:151], off offset:1536 nt
	global_load_dwordx2 v[118:119], v[16:17], off offset:2048 nt
	global_load_dwordx2 v[114:115], v[94:95], off offset:2048 nt
	global_load_dwordx2 v[40:41], v[150:151], off offset:2048 nt
	global_load_dwordx2 v[110:111], v[16:17], off offset:2560 nt
	global_load_dwordx2 v[106:107], v[94:95], off offset:2560 nt
	global_load_dwordx2 v[24:25], v[150:151], off offset:2560 nt
	global_load_dwordx2 v[102:103], v[16:17], off offset:3072 nt
	global_load_dwordx2 v[98:99], v[94:95], off offset:3072 nt
	global_load_dwordx2 v[20:21], v[150:151], off offset:3072 nt
	global_load_dwordx2 v[90:91], v[16:17], off offset:3584 nt
	s_nop 0
	global_load_dwordx2 v[94:95], v[94:95], off offset:3584 nt
	s_nop 0
	global_load_dwordx2 v[16:17], v[150:151], off offset:3584 nt
	v_lshlrev_b32_e32 v150, 16, v146
	v_and_b32_e32 v151, 0xffff0000, v146
	v_lshlrev_b32_e32 v146, 16, v147
	v_and_b32_e32 v147, 0xffff0000, v147
	v_add_f32_e32 v150, v150, v152
	v_add_f32_e32 v151, v151, v153
	v_add_f32_e32 v146, v146, v144
	v_add_f32_e32 v147, v147, v145
	v_mov_b32_e32 v152, v151
	v_mov_b32_e32 v153, v147
	v_mov_b32_e32 v144, v150
	v_mov_b32_e32 v145, v146
	v_mul_f32_e32 v152, v152, v152
	v_mul_f32_e32 v153, v153, v153
	s_nop 0
	v_fma_f32 v144, v144, v144, v152
	v_fma_f32 v145, v145, v145, v153
	v_lshlrev_b32_e32 v152, 16, v138
	v_add_f32_e32 v162, v144, v145
	v_lshlrev_b32_e32 v144, 16, v140
	v_and_b32_e32 v145, 0xffff0000, v140
	v_and_b32_e32 v153, 0xffff0000, v138
	v_lshlrev_b32_e32 v140, 16, v141
	v_and_b32_e32 v141, 0xffff0000, v141
	v_lshlrev_b32_e32 v138, 16, v139
	v_and_b32_e32 v139, 0xffff0000, v139
	v_add_f32_e32 v144, v144, v152
	v_add_f32_e32 v145, v145, v153
	v_add_f32_e32 v140, v140, v138
	v_add_f32_e32 v141, v141, v139
	v_mov_b32_e32 v152, v145
	v_mov_b32_e32 v153, v141
	v_mov_b32_e32 v138, v144
	v_mov_b32_e32 v139, v140
	v_mul_f32_e32 v152, v152, v152
	v_mul_f32_e32 v153, v153, v153
	s_nop 0
	v_fma_f32 v138, v138, v138, v152
	v_fma_f32 v139, v139, v139, v153
	v_lshlrev_b32_e32 v152, 16, v132
	v_add_f32_e32 v164, v138, v139
	v_lshlrev_b32_e32 v138, 16, v134
	v_and_b32_e32 v139, 0xffff0000, v134
	v_and_b32_e32 v153, 0xffff0000, v132
	v_lshlrev_b32_e32 v134, 16, v135
	v_and_b32_e32 v135, 0xffff0000, v135
	v_lshlrev_b32_e32 v132, 16, v133
	v_and_b32_e32 v133, 0xffff0000, v133
	v_add_f32_e32 v138, v138, v152
	v_add_f32_e32 v139, v139, v153
	v_add_f32_e32 v134, v134, v132
	v_add_f32_e32 v135, v135, v133
	v_mov_b32_e32 v152, v139
	v_mov_b32_e32 v153, v135
	v_mov_b32_e32 v132, v138
	v_mov_b32_e32 v133, v134
	v_mul_f32_e32 v152, v152, v152
	v_mul_f32_e32 v153, v153, v153
	s_nop 0
	v_fma_f32 v132, v132, v132, v152
	v_fma_f32 v133, v133, v133, v153
	v_lshlrev_b32_e32 v152, 16, v124
	v_add_f32_e32 v165, v132, v133
	v_lshlrev_b32_e32 v132, 16, v128
	v_and_b32_e32 v133, 0xffff0000, v128
	v_and_b32_e32 v153, 0xffff0000, v124
	v_lshlrev_b32_e32 v128, 16, v129
	v_and_b32_e32 v129, 0xffff0000, v129
	v_lshlrev_b32_e32 v124, 16, v125
	v_and_b32_e32 v125, 0xffff0000, v125
	v_add_f32_e32 v132, v132, v152
	v_add_f32_e32 v133, v133, v153
	v_add_f32_e32 v128, v128, v124
	v_add_f32_e32 v129, v129, v125
	v_mov_b32_e32 v152, v133
	v_mov_b32_e32 v153, v129
	v_mov_b32_e32 v124, v132
	v_mov_b32_e32 v125, v128
	v_mul_f32_e32 v152, v152, v152
	v_mul_f32_e32 v153, v153, v153
	s_nop 0
	v_fma_f32 v124, v124, v124, v152
	v_fma_f32 v125, v125, v125, v153
	v_lshlrev_b32_e32 v152, 16, v116
	v_add_f32_e32 v166, v124, v125
	v_lshlrev_b32_e32 v124, 16, v120
	v_and_b32_e32 v125, 0xffff0000, v120
	v_and_b32_e32 v153, 0xffff0000, v116
	v_lshlrev_b32_e32 v120, 16, v121
	v_and_b32_e32 v121, 0xffff0000, v121
	v_lshlrev_b32_e32 v116, 16, v117
	v_and_b32_e32 v117, 0xffff0000, v117
	v_add_f32_e32 v124, v124, v152
	v_add_f32_e32 v125, v125, v153
	v_add_f32_e32 v120, v120, v116
	v_add_f32_e32 v121, v121, v117
	v_mov_b32_e32 v152, v125
	v_mov_b32_e32 v153, v121
	v_mov_b32_e32 v116, v124
	v_mov_b32_e32 v117, v120
	v_mul_f32_e32 v152, v152, v152
	v_mul_f32_e32 v153, v153, v153
	s_nop 0
	v_fma_f32 v116, v116, v116, v152
	v_fma_f32 v117, v117, v117, v153
	v_lshlrev_b32_e32 v152, 16, v108
	v_add_f32_e32 v157, v116, v117
	v_lshlrev_b32_e32 v116, 16, v112
	v_and_b32_e32 v117, 0xffff0000, v112
	v_and_b32_e32 v153, 0xffff0000, v108
	v_lshlrev_b32_e32 v112, 16, v113
	v_and_b32_e32 v113, 0xffff0000, v113
	v_lshlrev_b32_e32 v108, 16, v109
	v_and_b32_e32 v109, 0xffff0000, v109
	v_add_f32_e32 v116, v116, v152
	v_add_f32_e32 v117, v117, v153
	v_add_f32_e32 v112, v112, v108
	v_add_f32_e32 v113, v113, v109
	v_mov_b32_e32 v152, v117
	v_mov_b32_e32 v153, v113
	v_mov_b32_e32 v108, v116
	v_mov_b32_e32 v109, v112
	v_mul_f32_e32 v152, v152, v152
	v_mul_f32_e32 v153, v153, v153
	s_nop 0
	v_fma_f32 v108, v108, v108, v152
	v_fma_f32 v109, v109, v109, v153
	v_lshlrev_b32_e32 v152, 16, v100
	v_add_f32_e32 v156, v108, v109
	v_lshlrev_b32_e32 v108, 16, v104
	v_and_b32_e32 v109, 0xffff0000, v104
	v_and_b32_e32 v153, 0xffff0000, v100
	v_lshlrev_b32_e32 v104, 16, v105
	v_and_b32_e32 v105, 0xffff0000, v105
	v_lshlrev_b32_e32 v100, 16, v101
	v_and_b32_e32 v101, 0xffff0000, v101
	v_add_f32_e32 v108, v108, v152
	v_add_f32_e32 v109, v109, v153
	v_add_f32_e32 v104, v104, v100
	v_add_f32_e32 v105, v105, v101
	v_mov_b32_e32 v152, v109
	v_mov_b32_e32 v153, v105
	v_mov_b32_e32 v100, v108
	v_mov_b32_e32 v101, v104
	v_mul_f32_e32 v152, v152, v152
	v_mul_f32_e32 v153, v153, v153
	s_nop 0
	v_fma_f32 v100, v100, v100, v152
	v_fma_f32 v101, v101, v101, v153
	s_nop 0
	v_add_f32_e32 v153, v100, v101
	v_lshlrev_b32_e32 v100, 16, v96
	v_and_b32_e32 v101, 0xffff0000, v96
	v_lshlrev_b32_e32 v96, 16, v97
	v_and_b32_e32 v97, 0xffff0000, v97
	v_add_f32_e32 v100, v100, v158
	v_add_f32_e32 v101, v101, v159
	v_add_f32_e32 v92, v96, v92
	v_add_f32_e32 v93, v97, v93
	v_mov_b32_e32 v158, v101
	v_mov_b32_e32 v159, v93
	v_mov_b32_e32 v96, v100
	v_mov_b32_e32 v97, v92
	v_mul_f32_e32 v158, v158, v158
	v_mul_f32_e32 v159, v159, v159
	s_nop 0
	v_fma_f32 v96, v96, v96, v158
	v_fma_f32 v97, v97, v97, v159
	v_add_f32_dpp v158, v162, v162 quad_perm:[1,0,3,2] row_mask:0xf bank_mask:0xf bound_ctrl:1
	v_add_f32_e32 v152, v96, v97
	v_lshl_add_u64 v[96:97], v[2:3], 0, s[16:17]
	v_add_f32_dpp v158, v158, v158 quad_perm:[2,3,0,1] row_mask:0xf bank_mask:0xf bound_ctrl:1
	v_lshl_add_u64 v[96:97], v[96:97], 0, v[0:1]
	s_nop 0
	v_add_f32_dpp v158, v158, v158 row_half_mirror row_mask:0xf bank_mask:0xf bound_ctrl:1
	s_nop 1
	v_add_f32_dpp v158, v158, v158 row_mirror row_mask:0xf bank_mask:0xf bound_ctrl:1
	s_nop 0
	v_readlane_b32 s9, v158, 16
	v_readlane_b32 s16, v158, 48
	v_readlane_b32 s6, v158, 0
	v_readlane_b32 s7, v158, 32
	v_mov_b32_e32 v158, s9
	v_mov_b32_e32 v159, s16
	v_add_f32_e32 v158, s6, v158
	v_add_f32_e32 v159, s7, v159
	s_nop 0
	v_add_f32_e32 v158, v158, v159
	v_fmamk_f32 v158, v158, 0x3b800000, v252
	v_cmp_gt_f32_e32 vcc, s55, v158
	v_mul_f32_e32 v159, 0x4f800000, v158
	s_nop 0
	v_cndmask_b32_e32 v158, v158, v159, vcc
	v_sqrt_f32_e32 v159, v158
	s_nop 0
	v_add_u32_e32 v162, -1, v159
	v_fma_f32 v163, -v162, v159, v158
	v_cmp_ge_f32_e64 s[6:7], 0, v163
	v_add_u32_e32 v163, 1, v159
	s_nop 0
	v_cndmask_b32_e64 v162, v159, v162, s[6:7]
	v_fma_f32 v159, -v163, v159, v158
	v_cmp_lt_f32_e64 s[6:7], 0, v159
	s_nop 1
	v_cndmask_b32_e64 v159, v162, v163, s[6:7]
	v_mul_f32_e32 v162, 0x37800000, v159
	v_cndmask_b32_e32 v159, v159, v162, vcc
	v_cmp_class_f32_e32 vcc, v158, v253
	s_nop 1
	v_cndmask_b32_e32 v158, v159, v158, vcc
	v_div_scale_f32 v159, s[6:7], v158, v158, 1.0
	v_rcp_f32_e32 v162, v159
	s_nop 0
	v_fma_f32 v163, -v159, v162, 1.0
	v_fmac_f32_e32 v162, v163, v162
	v_div_scale_f32 v163, vcc, 1.0, v158, 1.0
	v_mul_f32_e32 v167, v163, v162
	v_fma_f32 v168, -v159, v167, v163
	v_fmac_f32_e32 v167, v168, v162
	v_fma_f32 v159, -v159, v167, v163
	v_div_fmas_f32 v159, v159, v162, v167
	v_div_fixup_f32 v158, v159, v158, 1.0
	v_lshlrev_b32_e32 v162, 16, v66
	v_and_b32_e32 v163, 0xffff0000, v66
	v_lshlrev_b32_e32 v66, 16, v67
	v_and_b32_e32 v67, 0xffff0000, v67
	v_mul_f32_e32 v150, v150, v158
	v_mul_f32_e32 v151, v151, v158
	v_mul_f32_e32 v146, v146, v158
	v_mul_f32_e32 v147, v147, v158
	s_nop 0
	v_mul_f32_e32 v66, v146, v66
	v_mul_f32_e32 v67, v147, v67
	v_mul_f32_e32 v146, v150, v162
	v_mul_f32_e32 v147, v151, v163
	s_nop 0
	v_cvt_pk_bf16_f32 v146, v146, v147
	v_cvt_pk_bf16_f32 v147, v66, v67
	v_add_f32_dpp v66, v164, v164 quad_perm:[1,0,3,2] row_mask:0xf bank_mask:0xf bound_ctrl:1
	global_store_dwordx2 v[96:97], v[146:147], off
	s_nop 0
	v_add_f32_dpp v66, v66, v66 quad_perm:[2,3,0,1] row_mask:0xf bank_mask:0xf bound_ctrl:1
	s_nop 1
	v_add_f32_dpp v66, v66, v66 row_half_mirror row_mask:0xf bank_mask:0xf bound_ctrl:1
	s_nop 1
	v_add_f32_dpp v66, v66, v66 row_mirror row_mask:0xf bank_mask:0xf bound_ctrl:1
	s_nop 0
	v_readlane_b32 s9, v66, 16
	v_readlane_b32 s16, v66, 48
	v_readlane_b32 s6, v66, 0
	v_readlane_b32 s7, v66, 32
	v_mov_b32_e32 v66, s9
	v_mov_b32_e32 v67, s16
	v_add_f32_e32 v66, s6, v66
	v_add_f32_e32 v67, s7, v67
	s_nop 0
	v_add_f32_e32 v66, v66, v67
	v_fmamk_f32 v66, v66, 0x3b800000, v252
	v_cmp_gt_f32_e32 vcc, s55, v66
	v_mul_f32_e32 v67, 0x4f800000, v66
	s_nop 0
	v_cndmask_b32_e32 v66, v66, v67, vcc
	v_sqrt_f32_e32 v67, v66
	s_nop 0
	v_add_u32_e32 v146, -1, v67
	v_fma_f32 v147, -v146, v67, v66
	v_cmp_ge_f32_e64 s[6:7], 0, v147
	v_add_u32_e32 v147, 1, v67
	s_nop 0
	v_cndmask_b32_e64 v146, v67, v146, s[6:7]
	v_fma_f32 v67, -v147, v67, v66
	v_cmp_lt_f32_e64 s[6:7], 0, v67
	s_nop 1
	v_cndmask_b32_e64 v67, v146, v147, s[6:7]
	v_mul_f32_e32 v146, 0x37800000, v67
	v_cndmask_b32_e32 v67, v67, v146, vcc
	v_cmp_class_f32_e32 vcc, v66, v253
	s_nop 1
	v_cndmask_b32_e32 v66, v67, v66, vcc
	v_div_scale_f32 v67, s[6:7], v66, v66, 1.0
	v_rcp_f32_e32 v146, v67
	s_nop 0
	v_fma_f32 v147, -v67, v146, 1.0
	v_fmac_f32_e32 v146, v147, v146
	v_div_scale_f32 v147, vcc, 1.0, v66, 1.0
	v_mul_f32_e32 v150, v147, v146
	v_fma_f32 v151, -v67, v150, v147
	v_fmac_f32_e32 v150, v151, v146
	v_fma_f32 v67, -v67, v150, v147
	v_div_fmas_f32 v67, v67, v146, v150
	v_div_fixup_f32 v66, v67, v66, 1.0
	v_lshlrev_b32_e32 v146, 16, v60
	v_and_b32_e32 v147, 0xffff0000, v60
	v_lshlrev_b32_e32 v60, 16, v61
	v_and_b32_e32 v61, 0xffff0000, v61
	v_mul_f32_e32 v144, v144, v66
	v_mul_f32_e32 v145, v145, v66
	v_mul_f32_e32 v67, v141, v66
	v_mul_f32_e32 v66, v140, v66
	s_nop 0
	v_mul_f32_e32 v60, v66, v60
	v_mul_f32_e32 v61, v67, v61
	v_mul_f32_e32 v66, v144, v146
	v_mul_f32_e32 v67, v145, v147
	s_nop 0
	v_cvt_pk_bf16_f32 v66, v66, v67
	v_cvt_pk_bf16_f32 v67, v60, v61
	v_add_f32_dpp v60, v165, v165 quad_perm:[1,0,3,2] row_mask:0xf bank_mask:0xf bound_ctrl:1
	global_store_dwordx2 v[96:97], v[66:67], off offset:512
	s_nop 0
	v_add_f32_dpp v60, v60, v60 quad_perm:[2,3,0,1] row_mask:0xf bank_mask:0xf bound_ctrl:1
	s_nop 1
	v_add_f32_dpp v60, v60, v60 row_half_mirror row_mask:0xf bank_mask:0xf bound_ctrl:1
	s_nop 1
	v_add_f32_dpp v60, v60, v60 row_mirror row_mask:0xf bank_mask:0xf bound_ctrl:1
	s_nop 0
	v_readlane_b32 s9, v60, 16
	v_readlane_b32 s16, v60, 48
	v_readlane_b32 s6, v60, 0
	v_readlane_b32 s7, v60, 32
	v_mov_b32_e32 v60, s9
	v_mov_b32_e32 v61, s16
	v_add_f32_e32 v60, s6, v60
	v_add_f32_e32 v61, s7, v61
	s_nop 0
	v_add_f32_e32 v60, v60, v61
	v_fmamk_f32 v60, v60, 0x3b800000, v252
	v_cmp_gt_f32_e32 vcc, s55, v60
	v_mul_f32_e32 v61, 0x4f800000, v60
	s_nop 0
	v_cndmask_b32_e32 v60, v60, v61, vcc
	v_sqrt_f32_e32 v61, v60
	s_nop 0
	v_add_u32_e32 v66, -1, v61
	v_fma_f32 v67, -v66, v61, v60
	v_cmp_ge_f32_e64 s[6:7], 0, v67
	v_add_u32_e32 v67, 1, v61
	s_nop 0
	v_cndmask_b32_e64 v66, v61, v66, s[6:7]
	v_fma_f32 v61, -v67, v61, v60
	v_cmp_lt_f32_e64 s[6:7], 0, v61
	s_nop 1
	v_cndmask_b32_e64 v61, v66, v67, s[6:7]
	v_mul_f32_e32 v66, 0x37800000, v61
	v_cndmask_b32_e32 v61, v61, v66, vcc
	v_cmp_class_f32_e32 vcc, v60, v253
	s_nop 1
	v_cndmask_b32_e32 v60, v61, v60, vcc
	v_div_scale_f32 v61, s[6:7], v60, v60, 1.0
	v_rcp_f32_e32 v66, v61
	s_nop 0
	v_fma_f32 v67, -v61, v66, 1.0
	v_fmac_f32_e32 v66, v67, v66
	v_div_scale_f32 v67, vcc, 1.0, v60, 1.0
	v_mul_f32_e32 v140, v67, v66
	v_fma_f32 v141, -v61, v140, v67
	v_fmac_f32_e32 v140, v141, v66
	v_fma_f32 v61, -v61, v140, v67
	v_div_fmas_f32 v61, v61, v66, v140
	v_div_fixup_f32 v60, v61, v60, 1.0
	v_lshlrev_b32_e32 v66, 16, v54
	v_and_b32_e32 v67, 0xffff0000, v54
	v_lshlrev_b32_e32 v54, 16, v55
	v_and_b32_e32 v55, 0xffff0000, v55
	v_mul_f32_e32 v138, v138, v60
	v_mul_f32_e32 v139, v139, v60
	v_mul_f32_e32 v61, v135, v60
	v_mul_f32_e32 v60, v134, v60
	s_waitcnt vmcnt(56)
	v_lshlrev_b32_e32 v140, 16, v86
	v_mul_f32_e32 v54, v60, v54
	v_mul_f32_e32 v55, v61, v55
	v_mul_f32_e32 v60, v138, v66
	v_mul_f32_e32 v61, v139, v67
	v_and_b32_e32 v141, 0xffff0000, v86
	v_cvt_pk_bf16_f32 v60, v60, v61
	v_cvt_pk_bf16_f32 v61, v54, v55
	v_add_f32_dpp v54, v166, v166 quad_perm:[1,0,3,2] row_mask:0xf bank_mask:0xf bound_ctrl:1
	global_store_dwordx2 v[96:97], v[60:61], off offset:1024
	v_lshlrev_b32_e32 v86, 16, v87
	v_add_f32_dpp v54, v54, v54 quad_perm:[2,3,0,1] row_mask:0xf bank_mask:0xf bound_ctrl:1
	v_and_b32_e32 v87, 0xffff0000, v87
	s_nop 0
	v_add_f32_dpp v54, v54, v54 row_half_mirror row_mask:0xf bank_mask:0xf bound_ctrl:1
	s_nop 1
	v_add_f32_dpp v54, v54, v54 row_mirror row_mask:0xf bank_mask:0xf bound_ctrl:1
	s_nop 0
	v_readlane_b32 s9, v54, 16
	v_readlane_b32 s16, v54, 48
	v_readlane_b32 s6, v54, 0
	v_readlane_b32 s7, v54, 32
	v_mov_b32_e32 v54, s9
	v_mov_b32_e32 v55, s16
	v_add_f32_e32 v54, s6, v54
	v_add_f32_e32 v55, s7, v55
	s_nop 0
	v_add_f32_e32 v54, v54, v55
	v_fmamk_f32 v54, v54, 0x3b800000, v252
	v_cmp_gt_f32_e32 vcc, s55, v54
	v_mul_f32_e32 v55, 0x4f800000, v54
	s_nop 0
	v_cndmask_b32_e32 v54, v54, v55, vcc
	v_sqrt_f32_e32 v55, v54
	s_nop 0
	v_add_u32_e32 v60, -1, v55
	v_fma_f32 v61, -v60, v55, v54
	v_cmp_ge_f32_e64 s[6:7], 0, v61
	v_add_u32_e32 v61, 1, v55
	s_nop 0
	v_cndmask_b32_e64 v60, v55, v60, s[6:7]
	v_fma_f32 v55, -v61, v55, v54
	v_cmp_lt_f32_e64 s[6:7], 0, v55
	s_nop 1
	v_cndmask_b32_e64 v55, v60, v61, s[6:7]
	v_mul_f32_e32 v60, 0x37800000, v55
	v_cndmask_b32_e32 v55, v55, v60, vcc
	v_cmp_class_f32_e32 vcc, v54, v253
	s_nop 1
	v_cndmask_b32_e32 v54, v55, v54, vcc
	v_div_scale_f32 v55, s[6:7], v54, v54, 1.0
	v_rcp_f32_e32 v60, v55
	s_nop 0
	v_fma_f32 v61, -v55, v60, 1.0
	v_fmac_f32_e32 v60, v61, v60
	v_div_scale_f32 v61, vcc, 1.0, v54, 1.0
	v_mul_f32_e32 v66, v61, v60
	v_fma_f32 v67, -v55, v66, v61
	v_fmac_f32_e32 v66, v67, v60
	v_fma_f32 v55, -v55, v66, v61
	v_div_fmas_f32 v55, v55, v60, v66
	v_div_fixup_f32 v54, v55, v54, 1.0
	v_lshlrev_b32_e32 v60, 16, v48
	v_and_b32_e32 v61, 0xffff0000, v48
	v_lshlrev_b32_e32 v48, 16, v49
	v_and_b32_e32 v49, 0xffff0000, v49
	v_mul_f32_e32 v66, v132, v54
	v_mul_f32_e32 v67, v133, v54
	v_mul_f32_e32 v55, v129, v54
	v_mul_f32_e32 v54, v128, v54
	s_nop 0
	v_mul_f32_e32 v48, v54, v48
	v_mul_f32_e32 v49, v55, v49
	v_mul_f32_e32 v54, v66, v60
	v_mul_f32_e32 v55, v67, v61
	s_nop 0
	v_cvt_pk_bf16_f32 v54, v54, v55
	v_cvt_pk_bf16_f32 v55, v48, v49
	v_add_f32_dpp v48, v157, v157 quad_perm:[1,0,3,2] row_mask:0xf bank_mask:0xf bound_ctrl:1
	global_store_dwordx2 v[96:97], v[54:55], off offset:1536
	s_nop 0
	v_add_f32_dpp v48, v48, v48 quad_perm:[2,3,0,1] row_mask:0xf bank_mask:0xf bound_ctrl:1
	s_nop 1
	v_add_f32_dpp v48, v48, v48 row_half_mirror row_mask:0xf bank_mask:0xf bound_ctrl:1
	s_nop 1
	v_add_f32_dpp v48, v48, v48 row_mirror row_mask:0xf bank_mask:0xf bound_ctrl:1
	s_nop 0
	v_readlane_b32 s9, v48, 16
	v_readlane_b32 s16, v48, 48
	v_readlane_b32 s6, v48, 0
	v_readlane_b32 s7, v48, 32
	v_mov_b32_e32 v48, s9
	v_mov_b32_e32 v49, s16
	v_add_f32_e32 v48, s6, v48
	v_add_f32_e32 v49, s7, v49
	s_nop 0
	v_add_f32_e32 v48, v48, v49
	v_fmamk_f32 v48, v48, 0x3b800000, v252
	v_cmp_gt_f32_e32 vcc, s55, v48
	v_mul_f32_e32 v49, 0x4f800000, v48
	s_nop 0
	v_cndmask_b32_e32 v48, v48, v49, vcc
	v_sqrt_f32_e32 v49, v48
	s_nop 0
	v_add_u32_e32 v54, -1, v49
	v_fma_f32 v55, -v54, v49, v48
	v_cmp_ge_f32_e64 s[6:7], 0, v55
	v_add_u32_e32 v55, 1, v49
	s_nop 0
	v_cndmask_b32_e64 v54, v49, v54, s[6:7]
	v_fma_f32 v49, -v55, v49, v48
	v_cmp_lt_f32_e64 s[6:7], 0, v49
	s_nop 1
	v_cndmask_b32_e64 v49, v54, v55, s[6:7]
	v_mul_f32_e32 v54, 0x37800000, v49
	v_cndmask_b32_e32 v49, v49, v54, vcc
	v_cmp_class_f32_e32 vcc, v48, v253
	s_nop 1
	v_cndmask_b32_e32 v48, v49, v48, vcc
	v_div_scale_f32 v49, s[6:7], v48, v48, 1.0
	v_rcp_f32_e32 v54, v49
	s_nop 0
	v_fma_f32 v55, -v49, v54, 1.0
	v_fmac_f32_e32 v54, v55, v54
	v_div_scale_f32 v55, vcc, 1.0, v48, 1.0
	v_mul_f32_e32 v60, v55, v54
	v_fma_f32 v61, -v49, v60, v55
	v_fmac_f32_e32 v60, v61, v54
	v_fma_f32 v49, -v49, v60, v55
	v_div_fmas_f32 v49, v49, v54, v60
	v_div_fixup_f32 v48, v49, v48, 1.0
	v_lshlrev_b32_e32 v54, 16, v42
	v_and_b32_e32 v55, 0xffff0000, v42
	v_lshlrev_b32_e32 v42, 16, v43
	v_and_b32_e32 v43, 0xffff0000, v43
	v_mul_f32_e32 v60, v124, v48
	v_mul_f32_e32 v61, v125, v48
	v_mul_f32_e32 v49, v121, v48
	v_mul_f32_e32 v48, v120, v48
	s_nop 0
	v_mul_f32_e32 v42, v48, v42
	v_mul_f32_e32 v43, v49, v43
	v_mul_f32_e32 v48, v60, v54
	v_mul_f32_e32 v49, v61, v55
	s_nop 0
	v_cvt_pk_bf16_f32 v48, v48, v49
	v_cvt_pk_bf16_f32 v49, v42, v43
	v_add_f32_dpp v42, v156, v156 quad_perm:[1,0,3,2] row_mask:0xf bank_mask:0xf bound_ctrl:1
	global_store_dwordx2 v[96:97], v[48:49], off offset:2048
	s_nop 0
	v_add_f32_dpp v42, v42, v42 quad_perm:[2,3,0,1] row_mask:0xf bank_mask:0xf bound_ctrl:1
	s_nop 1
	v_add_f32_dpp v42, v42, v42 row_half_mirror row_mask:0xf bank_mask:0xf bound_ctrl:1
	s_nop 1
	v_add_f32_dpp v42, v42, v42 row_mirror row_mask:0xf bank_mask:0xf bound_ctrl:1
	s_nop 0
	v_readlane_b32 s9, v42, 16
	v_readlane_b32 s16, v42, 48
	v_readlane_b32 s6, v42, 0
	v_readlane_b32 s7, v42, 32
	v_mov_b32_e32 v42, s9
	v_mov_b32_e32 v43, s16
	v_add_f32_e32 v42, s6, v42
	v_add_f32_e32 v43, s7, v43
	s_nop 0
	v_add_f32_e32 v42, v42, v43
	v_fmamk_f32 v42, v42, 0x3b800000, v252
	v_cmp_gt_f32_e32 vcc, s55, v42
	v_mul_f32_e32 v43, 0x4f800000, v42
	s_nop 0
	v_cndmask_b32_e32 v42, v42, v43, vcc
	v_sqrt_f32_e32 v43, v42
	s_nop 0
	v_add_u32_e32 v48, -1, v43
	v_fma_f32 v49, -v48, v43, v42
	v_cmp_ge_f32_e64 s[6:7], 0, v49
	v_add_u32_e32 v49, 1, v43
	s_nop 0
	v_cndmask_b32_e64 v48, v43, v48, s[6:7]
	v_fma_f32 v43, -v49, v43, v42
	v_cmp_lt_f32_e64 s[6:7], 0, v43
	s_nop 1
	v_cndmask_b32_e64 v43, v48, v49, s[6:7]
	v_mul_f32_e32 v48, 0x37800000, v43
	v_cndmask_b32_e32 v43, v43, v48, vcc
	v_cmp_class_f32_e32 vcc, v42, v253
	s_nop 1
	v_cndmask_b32_e32 v42, v43, v42, vcc
	v_div_scale_f32 v43, s[6:7], v42, v42, 1.0
	v_rcp_f32_e32 v48, v43
	s_nop 0
	v_fma_f32 v49, -v43, v48, 1.0
	v_fmac_f32_e32 v48, v49, v48
	v_div_scale_f32 v49, vcc, 1.0, v42, 1.0
	v_mul_f32_e32 v54, v49, v48
	v_fma_f32 v55, -v43, v54, v49
	v_fmac_f32_e32 v54, v55, v48
	v_fma_f32 v43, -v43, v54, v49
	v_div_fmas_f32 v43, v43, v48, v54
	v_div_fixup_f32 v42, v43, v42, 1.0
	v_lshlrev_b32_e32 v48, 16, v36
	v_and_b32_e32 v49, 0xffff0000, v36
	v_lshlrev_b32_e32 v36, 16, v37
	v_and_b32_e32 v37, 0xffff0000, v37
	v_mul_f32_e32 v54, v116, v42
	v_mul_f32_e32 v55, v117, v42
	v_mul_f32_e32 v43, v113, v42
	v_mul_f32_e32 v42, v112, v42
	s_nop 0
	v_mul_f32_e32 v36, v42, v36
	v_mul_f32_e32 v37, v43, v37
	v_mul_f32_e32 v42, v54, v48
	v_mul_f32_e32 v43, v55, v49
	s_nop 0
	v_cvt_pk_bf16_f32 v42, v42, v43
	v_cvt_pk_bf16_f32 v43, v36, v37
	v_add_f32_dpp v36, v153, v153 quad_perm:[1,0,3,2] row_mask:0xf bank_mask:0xf bound_ctrl:1
	global_store_dwordx2 v[96:97], v[42:43], off offset:2560
	s_waitcnt vmcnt(39)
	v_and_b32_e32 v153, 0xffff0000, v44
	v_add_f32_dpp v36, v36, v36 quad_perm:[2,3,0,1] row_mask:0xf bank_mask:0xf bound_ctrl:1
	s_nop 1
	v_add_f32_dpp v36, v36, v36 row_half_mirror row_mask:0xf bank_mask:0xf bound_ctrl:1
	s_nop 1
	v_add_f32_dpp v36, v36, v36 row_mirror row_mask:0xf bank_mask:0xf bound_ctrl:1
	s_nop 0
	v_readlane_b32 s9, v36, 16
	v_readlane_b32 s16, v36, 48
	v_readlane_b32 s6, v36, 0
	v_readlane_b32 s7, v36, 32
	v_mov_b32_e32 v36, s9
	v_mov_b32_e32 v37, s16
	v_add_f32_e32 v36, s6, v36
	v_add_f32_e32 v37, s7, v37
	s_nop 0
	v_add_f32_e32 v36, v36, v37
	v_fmamk_f32 v36, v36, 0x3b800000, v252
	v_cmp_gt_f32_e32 vcc, s55, v36
	v_mul_f32_e32 v37, 0x4f800000, v36
	s_nop 0
	v_cndmask_b32_e32 v36, v36, v37, vcc
	v_sqrt_f32_e32 v37, v36
	s_nop 0
	v_add_u32_e32 v42, -1, v37
	v_fma_f32 v43, -v42, v37, v36
	v_cmp_ge_f32_e64 s[6:7], 0, v43
	v_add_u32_e32 v43, 1, v37
	s_nop 0
	v_cndmask_b32_e64 v42, v37, v42, s[6:7]
	v_fma_f32 v37, -v43, v37, v36
	v_cmp_lt_f32_e64 s[6:7], 0, v37
	s_nop 1
	v_cndmask_b32_e64 v37, v42, v43, s[6:7]
	v_mul_f32_e32 v42, 0x37800000, v37
	v_cndmask_b32_e32 v37, v37, v42, vcc
	v_cmp_class_f32_e32 vcc, v36, v253
	s_nop 1
	v_cndmask_b32_e32 v36, v37, v36, vcc
	v_div_scale_f32 v37, s[6:7], v36, v36, 1.0
	v_rcp_f32_e32 v42, v37
	s_nop 0
	v_fma_f32 v43, -v37, v42, 1.0
	v_fmac_f32_e32 v42, v43, v42
	v_div_scale_f32 v43, vcc, 1.0, v36, 1.0
	v_mul_f32_e32 v48, v43, v42
	v_fma_f32 v49, -v37, v48, v43
	v_fmac_f32_e32 v48, v49, v42
	v_fma_f32 v37, -v37, v48, v43
	v_div_fmas_f32 v37, v37, v42, v48
	v_div_fixup_f32 v36, v37, v36, 1.0
	v_lshlrev_b32_e32 v42, 16, v32
	v_and_b32_e32 v43, 0xffff0000, v32
	v_lshlrev_b32_e32 v32, 16, v33
	v_and_b32_e32 v33, 0xffff0000, v33
	v_mul_f32_e32 v48, v108, v36
	v_mul_f32_e32 v49, v109, v36
	v_mul_f32_e32 v37, v105, v36
	v_mul_f32_e32 v36, v104, v36
	s_nop 0
	v_mul_f32_e32 v32, v36, v32
	v_mul_f32_e32 v33, v37, v33
	v_mul_f32_e32 v36, v48, v42
	v_mul_f32_e32 v37, v49, v43
	s_nop 0
	v_cvt_pk_bf16_f32 v36, v36, v37
	v_cvt_pk_bf16_f32 v37, v32, v33
	v_add_f32_dpp v32, v152, v152 quad_perm:[1,0,3,2] row_mask:0xf bank_mask:0xf bound_ctrl:1
	global_store_dwordx2 v[96:97], v[36:37], off offset:3072
	v_lshlrev_b32_e32 v152, 16, v44
	v_add_f32_dpp v32, v32, v32 quad_perm:[2,3,0,1] row_mask:0xf bank_mask:0xf bound_ctrl:1
	v_lshlrev_b32_e32 v44, 16, v45
	v_and_b32_e32 v45, 0xffff0000, v45
	v_add_f32_dpp v32, v32, v32 row_half_mirror row_mask:0xf bank_mask:0xf bound_ctrl:1
	s_nop 1
	v_add_f32_dpp v32, v32, v32 row_mirror row_mask:0xf bank_mask:0xf bound_ctrl:1
	s_nop 0
	v_readlane_b32 s9, v32, 16
	v_readlane_b32 s16, v32, 48
	v_readlane_b32 s6, v32, 0
	v_readlane_b32 s7, v32, 32
	v_mov_b32_e32 v32, s9
	v_mov_b32_e32 v33, s16
	v_add_f32_e32 v32, s6, v32
	v_add_f32_e32 v33, s7, v33
	s_add_u32 s16, s10, 0x2000000
	v_add_f32_e32 v32, v32, v33
	v_fmamk_f32 v32, v32, 0x3b800000, v252
	v_cmp_gt_f32_e32 vcc, s55, v32
	v_mul_f32_e32 v33, 0x4f800000, v32
	s_addc_u32 s17, s11, 0
	v_cndmask_b32_e32 v32, v32, v33, vcc
	v_sqrt_f32_e32 v33, v32
	s_nop 0
	v_add_u32_e32 v36, -1, v33
	v_fma_f32 v37, -v36, v33, v32
	v_cmp_ge_f32_e64 s[6:7], 0, v37
	v_add_u32_e32 v37, 1, v33
	s_nop 0
	v_cndmask_b32_e64 v36, v33, v36, s[6:7]
	v_fma_f32 v33, -v37, v33, v32
	v_cmp_lt_f32_e64 s[6:7], 0, v33
	s_nop 1
	v_cndmask_b32_e64 v33, v36, v37, s[6:7]
	v_mul_f32_e32 v36, 0x37800000, v33
	v_cndmask_b32_e32 v33, v33, v36, vcc
	v_cmp_class_f32_e32 vcc, v32, v253
	s_nop 1
	v_cndmask_b32_e32 v32, v33, v32, vcc
	v_div_scale_f32 v33, s[6:7], v32, v32, 1.0
	v_rcp_f32_e32 v36, v33
	s_nop 0
	v_fma_f32 v37, -v33, v36, 1.0
	v_fmac_f32_e32 v36, v37, v36
	v_div_scale_f32 v37, vcc, 1.0, v32, 1.0
	v_mul_f32_e32 v42, v37, v36
	v_fma_f32 v43, -v33, v42, v37
	v_fmac_f32_e32 v42, v43, v36
	v_fma_f32 v33, -v33, v42, v37
	v_div_fmas_f32 v33, v33, v36, v42
	v_div_fixup_f32 v32, v33, v32, 1.0
	v_lshlrev_b32_e32 v36, 16, v28
	v_and_b32_e32 v37, 0xffff0000, v28
	v_lshlrev_b32_e32 v28, 16, v29
	v_and_b32_e32 v29, 0xffff0000, v29
	v_mul_f32_e32 v42, v100, v32
	v_mul_f32_e32 v43, v101, v32
	v_mul_f32_e32 v33, v93, v32
	v_mul_f32_e32 v32, v92, v32
	s_nop 0
	v_mul_f32_e32 v28, v32, v28
	v_mul_f32_e32 v29, v33, v29
	v_mul_f32_e32 v32, v42, v36
	v_mul_f32_e32 v33, v43, v37
	s_nop 0
	v_cvt_pk_bf16_f32 v32, v32, v33
	v_cvt_pk_bf16_f32 v33, v28, v29
	global_store_dwordx2 v[96:97], v[32:33], off offset:3584
	v_lshl_add_u64 v[32:33], v[6:7], 0, s[16:17]
	v_lshl_add_u64 v[28:29], v[4:5], 0, s[16:17]
	v_lshl_add_u64 v[96:97], v[32:33], 0, v[0:1]
	v_lshl_add_u64 v[32:33], v[8:9], 0, s[16:17]
	v_lshl_add_u64 v[28:29], v[28:29], 0, v[0:1]
	v_lshl_add_u64 v[134:135], v[32:33], 0, v[0:1]
	global_load_dwordx2 v[162:163], v[28:29], off nt
	global_load_dwordx2 v[156:157], v[96:97], off nt
	global_load_dwordx2 v[66:67], v[134:135], off nt
	global_load_dwordx2 v[150:151], v[28:29], off offset:512 nt
	global_load_dwordx2 v[144:145], v[96:97], off offset:512 nt
	global_load_dwordx2 v[60:61], v[134:135], off offset:512 nt
	global_load_dwordx2 v[138:139], v[28:29], off offset:1024 nt
	global_load_dwordx2 v[132:133], v[96:97], off offset:1024 nt
	global_load_dwordx2 v[54:55], v[134:135], off offset:1024 nt
	global_load_dwordx2 v[124:125], v[28:29], off offset:1536 nt
	global_load_dwordx2 v[128:129], v[96:97], off offset:1536 nt
	global_load_dwordx2 v[48:49], v[134:135], off offset:1536 nt
	global_load_dwordx2 v[120:121], v[28:29], off offset:2048 nt
	global_load_dwordx2 v[116:117], v[96:97], off offset:2048 nt
	global_load_dwordx2 v[42:43], v[134:135], off offset:2048 nt
	global_load_dwordx2 v[112:113], v[28:29], off offset:2560 nt
	global_load_dwordx2 v[108:109], v[96:97], off offset:2560 nt
	global_load_dwordx2 v[36:37], v[134:135], off offset:2560 nt
	global_load_dwordx2 v[104:105], v[28:29], off offset:3072 nt
	global_load_dwordx2 v[100:101], v[96:97], off offset:3072 nt
	global_load_dwordx2 v[32:33], v[134:135], off offset:3072 nt
	global_load_dwordx2 v[92:93], v[28:29], off offset:3584 nt
	s_nop 0
	global_load_dwordx2 v[96:97], v[96:97], off offset:3584 nt
	s_nop 0
	global_load_dwordx2 v[28:29], v[134:135], off offset:3584 nt
	v_lshlrev_b32_e32 v134, 16, v88
	v_and_b32_e32 v135, 0xffff0000, v88
	v_lshlrev_b32_e32 v88, 16, v89
	v_and_b32_e32 v89, 0xffff0000, v89
	v_add_f32_e32 v134, v134, v140
	v_add_f32_e32 v135, v135, v141
	v_add_f32_e32 v88, v88, v86
	v_add_f32_e32 v89, v89, v87
	v_mov_b32_e32 v140, v135
	v_mov_b32_e32 v141, v89
	v_mov_b32_e32 v86, v134
	v_mov_b32_e32 v87, v88
	v_mul_f32_e32 v140, v140, v140
	v_mul_f32_e32 v141, v141, v141
	s_nop 0
	v_fma_f32 v86, v86, v86, v140
	v_fma_f32 v87, v87, v87, v141
	v_lshlrev_b32_e32 v140, 16, v82
	v_add_f32_e32 v158, v86, v87
	v_lshlrev_b32_e32 v86, 16, v84
	v_and_b32_e32 v87, 0xffff0000, v84
	v_and_b32_e32 v141, 0xffff0000, v82
	v_lshlrev_b32_e32 v84, 16, v85
	v_and_b32_e32 v85, 0xffff0000, v85
	v_lshlrev_b32_e32 v82, 16, v83
	v_and_b32_e32 v83, 0xffff0000, v83
	v_add_f32_e32 v86, v86, v140
	v_add_f32_e32 v87, v87, v141
	v_add_f32_e32 v84, v84, v82
	v_add_f32_e32 v85, v85, v83
	v_mov_b32_e32 v140, v87
	v_mov_b32_e32 v141, v85
	v_mov_b32_e32 v82, v86
	v_mov_b32_e32 v83, v84
	v_mul_f32_e32 v140, v140, v140
	v_mul_f32_e32 v141, v141, v141
	s_nop 0
	v_fma_f32 v82, v82, v82, v140
	v_fma_f32 v83, v83, v83, v141
	v_lshlrev_b32_e32 v140, 16, v78
	v_add_f32_e32 v164, v82, v83
	v_lshlrev_b32_e32 v82, 16, v80
	v_and_b32_e32 v83, 0xffff0000, v80
	v_and_b32_e32 v141, 0xffff0000, v78
	v_lshlrev_b32_e32 v80, 16, v81
	v_and_b32_e32 v81, 0xffff0000, v81
	v_lshlrev_b32_e32 v78, 16, v79
	v_and_b32_e32 v79, 0xffff0000, v79
	v_add_f32_e32 v82, v82, v140
	v_add_f32_e32 v83, v83, v141
	v_add_f32_e32 v80, v80, v78
	v_add_f32_e32 v81, v81, v79
	v_mov_b32_e32 v140, v83
	v_mov_b32_e32 v141, v81
	v_mov_b32_e32 v78, v82
	v_mov_b32_e32 v79, v80
	v_mul_f32_e32 v140, v140, v140
	v_mul_f32_e32 v141, v141, v141
	s_nop 0
	v_fma_f32 v78, v78, v78, v140
	v_fma_f32 v79, v79, v79, v141
	v_lshlrev_b32_e32 v140, 16, v76
	v_add_f32_e32 v165, v78, v79
	v_lshlrev_b32_e32 v78, 16, v74
	v_and_b32_e32 v79, 0xffff0000, v74
	v_and_b32_e32 v141, 0xffff0000, v76
	v_lshlrev_b32_e32 v74, 16, v75
	v_and_b32_e32 v75, 0xffff0000, v75
	v_lshlrev_b32_e32 v76, 16, v77
	v_and_b32_e32 v77, 0xffff0000, v77
	v_add_f32_e32 v78, v78, v140
	v_add_f32_e32 v79, v79, v141
	v_add_f32_e32 v76, v74, v76
	v_add_f32_e32 v77, v75, v77
	v_mov_b32_e32 v140, v79
	v_mov_b32_e32 v141, v77
	v_mov_b32_e32 v74, v78
	v_mov_b32_e32 v75, v76
	v_mul_f32_e32 v140, v140, v140
	v_mul_f32_e32 v141, v141, v141
	s_nop 0
	v_fma_f32 v74, v74, v74, v140
	v_fma_f32 v75, v75, v75, v141
	v_lshlrev_b32_e32 v140, 16, v70
	v_add_f32_e32 v166, v74, v75
	v_lshlrev_b32_e32 v74, 16, v72
	v_and_b32_e32 v75, 0xffff0000, v72
	v_and_b32_e32 v141, 0xffff0000, v70
	v_lshlrev_b32_e32 v72, 16, v73
	v_and_b32_e32 v73, 0xffff0000, v73
	v_lshlrev_b32_e32 v70, 16, v71
	v_and_b32_e32 v71, 0xffff0000, v71
	v_add_f32_e32 v74, v74, v140
	v_add_f32_e32 v75, v75, v141
	v_add_f32_e32 v72, v72, v70
	v_add_f32_e32 v73, v73, v71
	v_mov_b32_e32 v140, v75
	v_mov_b32_e32 v141, v73
	v_mov_b32_e32 v70, v74
	v_mov_b32_e32 v71, v72
	v_mul_f32_e32 v140, v140, v140
	v_mul_f32_e32 v141, v141, v141
	s_nop 0
	v_fma_f32 v70, v70, v70, v140
	v_fma_f32 v71, v71, v71, v141
	v_lshlrev_b32_e32 v140, 16, v62
	v_add_f32_e32 v147, v70, v71
	v_lshlrev_b32_e32 v70, 16, v68
	v_and_b32_e32 v71, 0xffff0000, v68
	v_and_b32_e32 v141, 0xffff0000, v62
	v_lshlrev_b32_e32 v68, 16, v69
	v_and_b32_e32 v69, 0xffff0000, v69
	v_lshlrev_b32_e32 v62, 16, v63
	v_and_b32_e32 v63, 0xffff0000, v63
	v_add_f32_e32 v70, v70, v140
	v_add_f32_e32 v71, v71, v141
	v_add_f32_e32 v68, v68, v62
	v_add_f32_e32 v69, v69, v63
	v_mov_b32_e32 v140, v71
	v_mov_b32_e32 v141, v69
	v_mov_b32_e32 v62, v70
	v_mov_b32_e32 v63, v68
	v_mul_f32_e32 v140, v140, v140
	v_mul_f32_e32 v141, v141, v141
	s_nop 0
	v_fma_f32 v62, v62, v62, v140
	v_fma_f32 v63, v63, v63, v141
	v_lshlrev_b32_e32 v140, 16, v50
	v_add_f32_e32 v146, v62, v63
	v_lshlrev_b32_e32 v62, 16, v56
	v_and_b32_e32 v63, 0xffff0000, v56
	v_and_b32_e32 v141, 0xffff0000, v50
	v_lshlrev_b32_e32 v56, 16, v57
	v_and_b32_e32 v57, 0xffff0000, v57
	v_lshlrev_b32_e32 v50, 16, v51
	v_and_b32_e32 v51, 0xffff0000, v51
	v_add_f32_e32 v62, v62, v140
	v_add_f32_e32 v63, v63, v141
	v_add_f32_e32 v56, v56, v50
	v_add_f32_e32 v57, v57, v51
	v_mov_b32_e32 v140, v63
	v_mov_b32_e32 v141, v57
	v_mov_b32_e32 v50, v62
	v_mov_b32_e32 v51, v56
	v_mul_f32_e32 v140, v140, v140
	v_mul_f32_e32 v141, v141, v141
	s_nop 0
	v_fma_f32 v50, v50, v50, v140
	v_fma_f32 v51, v51, v51, v141
	s_nop 0
	v_add_f32_e32 v141, v50, v51
	v_lshlrev_b32_e32 v50, 16, v38
	v_and_b32_e32 v51, 0xffff0000, v38
	v_lshlrev_b32_e32 v38, 16, v39
	v_and_b32_e32 v39, 0xffff0000, v39
	v_add_f32_e32 v50, v50, v152
	v_add_f32_e32 v51, v51, v153
	v_add_f32_e32 v38, v38, v44
	v_add_f32_e32 v39, v39, v45
	v_mov_b32_e32 v152, v51
	v_mov_b32_e32 v153, v39
	v_mov_b32_e32 v44, v50
	v_mov_b32_e32 v45, v38
	v_mul_f32_e32 v152, v152, v152
	v_mul_f32_e32 v153, v153, v153
	s_nop 0
	v_fma_f32 v44, v44, v44, v152
	v_fma_f32 v45, v45, v45, v153
	v_add_f32_dpp v152, v158, v158 quad_perm:[1,0,3,2] row_mask:0xf bank_mask:0xf bound_ctrl:1
	v_add_f32_e32 v140, v44, v45
	v_lshl_add_u64 v[44:45], v[2:3], 0, s[12:13]
	v_add_f32_dpp v152, v152, v152 quad_perm:[2,3,0,1] row_mask:0xf bank_mask:0xf bound_ctrl:1
	v_lshl_add_u64 v[44:45], v[44:45], 0, v[0:1]
	s_nop 0
	v_add_f32_dpp v152, v152, v152 row_half_mirror row_mask:0xf bank_mask:0xf bound_ctrl:1
	s_nop 1
	v_add_f32_dpp v152, v152, v152 row_mirror row_mask:0xf bank_mask:0xf bound_ctrl:1
	s_nop 0
	v_readlane_b32 s9, v152, 16
	v_readlane_b32 s12, v152, 48
	v_readlane_b32 s6, v152, 0
	v_readlane_b32 s7, v152, 32
	v_mov_b32_e32 v152, s9
	v_mov_b32_e32 v153, s12
	v_add_f32_e32 v152, s6, v152
	v_add_f32_e32 v153, s7, v153
	s_nop 0
	v_add_f32_e32 v152, v152, v153
	v_fmamk_f32 v152, v152, 0x3b800000, v252
	v_cmp_gt_f32_e32 vcc, s55, v152
	v_mul_f32_e32 v153, 0x4f800000, v152
	s_nop 0
	v_cndmask_b32_e32 v152, v152, v153, vcc
	v_sqrt_f32_e32 v153, v152
	s_nop 0
	v_add_u32_e32 v158, -1, v153
	v_fma_f32 v159, -v158, v153, v152
	v_cmp_ge_f32_e64 s[6:7], 0, v159
	v_add_u32_e32 v159, 1, v153
	s_nop 0
	v_cndmask_b32_e64 v158, v153, v158, s[6:7]
	v_fma_f32 v153, -v159, v153, v152
	v_cmp_lt_f32_e64 s[6:7], 0, v153
	s_nop 1
	v_cndmask_b32_e64 v153, v158, v159, s[6:7]
	v_mul_f32_e32 v158, 0x37800000, v153
	v_cndmask_b32_e32 v153, v153, v158, vcc
	v_cmp_class_f32_e32 vcc, v152, v253
	s_nop 1
	v_cndmask_b32_e32 v152, v153, v152, vcc
	v_div_scale_f32 v153, s[6:7], v152, v152, 1.0
	v_rcp_f32_e32 v158, v153
	s_nop 0
	v_fma_f32 v159, -v153, v158, 1.0
	v_fmac_f32_e32 v158, v159, v158
	v_div_scale_f32 v159, vcc, 1.0, v152, 1.0
	v_mul_f32_e32 v167, v159, v158
	v_fma_f32 v168, -v153, v167, v159
	v_fmac_f32_e32 v167, v168, v158
	v_fma_f32 v153, -v153, v167, v159
	v_div_fmas_f32 v153, v153, v158, v167
	v_div_fixup_f32 v152, v153, v152, 1.0
	v_lshlrev_b32_e32 v158, 16, v34
	v_and_b32_e32 v159, 0xffff0000, v34
	v_lshlrev_b32_e32 v34, 16, v35
	v_and_b32_e32 v35, 0xffff0000, v35
	v_mul_f32_e32 v134, v134, v152
	v_mul_f32_e32 v135, v135, v152
	v_mul_f32_e32 v88, v88, v152
	v_mul_f32_e32 v89, v89, v152
	s_nop 0
	v_mul_f32_e32 v34, v88, v34
	v_mul_f32_e32 v35, v89, v35
	v_mul_f32_e32 v88, v134, v158
	v_mul_f32_e32 v89, v135, v159
	s_nop 0
	v_cvt_pk_bf16_f32 v88, v88, v89
	v_cvt_pk_bf16_f32 v89, v34, v35
	v_add_f32_dpp v34, v164, v164 quad_perm:[1,0,3,2] row_mask:0xf bank_mask:0xf bound_ctrl:1
	global_store_dwordx2 v[44:45], v[88:89], off
	s_nop 0
	v_add_f32_dpp v34, v34, v34 quad_perm:[2,3,0,1] row_mask:0xf bank_mask:0xf bound_ctrl:1
	s_nop 1
	v_add_f32_dpp v34, v34, v34 row_half_mirror row_mask:0xf bank_mask:0xf bound_ctrl:1
	s_nop 1
	v_add_f32_dpp v34, v34, v34 row_mirror row_mask:0xf bank_mask:0xf bound_ctrl:1
	s_nop 0
	v_readlane_b32 s9, v34, 16
	v_readlane_b32 s12, v34, 48
	v_readlane_b32 s6, v34, 0
	v_readlane_b32 s7, v34, 32
	v_mov_b32_e32 v34, s9
	v_mov_b32_e32 v35, s12
	v_add_f32_e32 v34, s6, v34
	v_add_f32_e32 v35, s7, v35
	s_nop 0
	v_add_f32_e32 v34, v34, v35
	v_fmamk_f32 v34, v34, 0x3b800000, v252
	v_cmp_gt_f32_e32 vcc, s55, v34
	v_mul_f32_e32 v35, 0x4f800000, v34
	s_nop 0
	v_cndmask_b32_e32 v34, v34, v35, vcc
	v_sqrt_f32_e32 v35, v34
	s_nop 0
	v_add_u32_e32 v88, -1, v35
	v_fma_f32 v89, -v88, v35, v34
	v_cmp_ge_f32_e64 s[6:7], 0, v89
	v_add_u32_e32 v89, 1, v35
	s_nop 0
	v_cndmask_b32_e64 v88, v35, v88, s[6:7]
	v_fma_f32 v35, -v89, v35, v34
	v_cmp_lt_f32_e64 s[6:7], 0, v35
	s_nop 1
	v_cndmask_b32_e64 v35, v88, v89, s[6:7]
	v_mul_f32_e32 v88, 0x37800000, v35
	v_cndmask_b32_e32 v35, v35, v88, vcc
	v_cmp_class_f32_e32 vcc, v34, v253
	s_nop 1
	v_cndmask_b32_e32 v34, v35, v34, vcc
	v_div_scale_f32 v35, s[6:7], v34, v34, 1.0
	v_rcp_f32_e32 v88, v35
	s_nop 0
	v_fma_f32 v89, -v35, v88, 1.0
	v_fmac_f32_e32 v88, v89, v88
	v_div_scale_f32 v89, vcc, 1.0, v34, 1.0
	v_mul_f32_e32 v134, v89, v88
	v_fma_f32 v135, -v35, v134, v89
	v_fmac_f32_e32 v134, v135, v88
	v_fma_f32 v35, -v35, v134, v89
	v_div_fmas_f32 v35, v35, v88, v134
	v_div_fixup_f32 v34, v35, v34, 1.0
	v_lshlrev_b32_e32 v88, 16, v30
	v_and_b32_e32 v89, 0xffff0000, v30
	v_lshlrev_b32_e32 v30, 16, v31
	v_and_b32_e32 v31, 0xffff0000, v31
	v_mul_f32_e32 v86, v86, v34
	v_mul_f32_e32 v87, v87, v34
	v_mul_f32_e32 v35, v85, v34
	v_mul_f32_e32 v34, v84, v34
	s_nop 0
	v_mul_f32_e32 v30, v34, v30
	v_mul_f32_e32 v31, v35, v31
	v_mul_f32_e32 v34, v86, v88
	v_mul_f32_e32 v35, v87, v89
	s_nop 0
	v_cvt_pk_bf16_f32 v34, v34, v35
	v_cvt_pk_bf16_f32 v35, v30, v31
	v_add_f32_dpp v30, v165, v165 quad_perm:[1,0,3,2] row_mask:0xf bank_mask:0xf bound_ctrl:1
	global_store_dwordx2 v[44:45], v[34:35], off offset:512
	s_nop 0
	v_add_f32_dpp v30, v30, v30 quad_perm:[2,3,0,1] row_mask:0xf bank_mask:0xf bound_ctrl:1
	s_nop 1
	v_add_f32_dpp v30, v30, v30 row_half_mirror row_mask:0xf bank_mask:0xf bound_ctrl:1
	s_nop 1
	v_add_f32_dpp v30, v30, v30 row_mirror row_mask:0xf bank_mask:0xf bound_ctrl:1
	s_nop 0
	v_readlane_b32 s9, v30, 16
	v_readlane_b32 s12, v30, 48
	v_readlane_b32 s6, v30, 0
	v_readlane_b32 s7, v30, 32
	v_mov_b32_e32 v30, s9
	v_mov_b32_e32 v31, s12
	v_add_f32_e32 v30, s6, v30
	v_add_f32_e32 v31, s7, v31
	s_nop 0
	v_add_f32_e32 v30, v30, v31
	v_fmamk_f32 v30, v30, 0x3b800000, v252
	v_cmp_gt_f32_e32 vcc, s55, v30
	v_mul_f32_e32 v31, 0x4f800000, v30
	s_nop 0
	v_cndmask_b32_e32 v30, v30, v31, vcc
	v_sqrt_f32_e32 v31, v30
	s_nop 0
	v_add_u32_e32 v34, -1, v31
	v_fma_f32 v35, -v34, v31, v30
	v_cmp_ge_f32_e64 s[6:7], 0, v35
	v_add_u32_e32 v35, 1, v31
	s_nop 0
	v_cndmask_b32_e64 v34, v31, v34, s[6:7]
	v_fma_f32 v31, -v35, v31, v30
	v_cmp_lt_f32_e64 s[6:7], 0, v31
	s_nop 1
	v_cndmask_b32_e64 v31, v34, v35, s[6:7]
	v_mul_f32_e32 v34, 0x37800000, v31
	v_cndmask_b32_e32 v31, v31, v34, vcc
	v_cmp_class_f32_e32 vcc, v30, v253
	s_nop 1
	v_cndmask_b32_e32 v30, v31, v30, vcc
	v_div_scale_f32 v31, s[6:7], v30, v30, 1.0
	v_rcp_f32_e32 v34, v31
	s_nop 0
	v_fma_f32 v35, -v31, v34, 1.0
	v_fmac_f32_e32 v34, v35, v34
	v_div_scale_f32 v35, vcc, 1.0, v30, 1.0
	v_mul_f32_e32 v84, v35, v34
	v_fma_f32 v85, -v31, v84, v35
	v_fmac_f32_e32 v84, v85, v34
	v_fma_f32 v31, -v31, v84, v35
	v_div_fmas_f32 v31, v31, v34, v84
	v_div_fixup_f32 v30, v31, v30, 1.0
	v_lshlrev_b32_e32 v34, 16, v26
	v_and_b32_e32 v35, 0xffff0000, v26
	v_lshlrev_b32_e32 v26, 16, v27
	v_and_b32_e32 v27, 0xffff0000, v27
	v_mul_f32_e32 v82, v82, v30
	v_mul_f32_e32 v83, v83, v30
	v_mul_f32_e32 v31, v81, v30
	v_mul_f32_e32 v30, v80, v30
	s_nop 0
	v_mul_f32_e32 v26, v30, v26
	v_mul_f32_e32 v27, v31, v27
	v_mul_f32_e32 v30, v82, v34
	v_mul_f32_e32 v31, v83, v35
	s_nop 0
	v_cvt_pk_bf16_f32 v30, v30, v31
	v_cvt_pk_bf16_f32 v31, v26, v27
	v_add_f32_dpp v26, v166, v166 quad_perm:[1,0,3,2] row_mask:0xf bank_mask:0xf bound_ctrl:1
	global_store_dwordx2 v[44:45], v[30:31], off offset:1024
	s_nop 0
	v_add_f32_dpp v26, v26, v26 quad_perm:[2,3,0,1] row_mask:0xf bank_mask:0xf bound_ctrl:1
	s_nop 1
	v_add_f32_dpp v26, v26, v26 row_half_mirror row_mask:0xf bank_mask:0xf bound_ctrl:1
	s_nop 1
	v_add_f32_dpp v26, v26, v26 row_mirror row_mask:0xf bank_mask:0xf bound_ctrl:1
	s_nop 0
	v_readlane_b32 s9, v26, 16
	v_readlane_b32 s12, v26, 48
	v_readlane_b32 s6, v26, 0
	v_readlane_b32 s7, v26, 32
	v_mov_b32_e32 v26, s9
	v_mov_b32_e32 v27, s12
	v_add_f32_e32 v26, s6, v26
	v_add_f32_e32 v27, s7, v27
	s_nop 0
	v_add_f32_e32 v26, v26, v27
	v_fmamk_f32 v26, v26, 0x3b800000, v252
	v_cmp_gt_f32_e32 vcc, s55, v26
	v_mul_f32_e32 v27, 0x4f800000, v26
	s_nop 0
	v_cndmask_b32_e32 v26, v26, v27, vcc
	v_sqrt_f32_e32 v27, v26
	s_nop 0
	v_add_u32_e32 v30, -1, v27
	v_fma_f32 v31, -v30, v27, v26
	v_cmp_ge_f32_e64 s[6:7], 0, v31
	v_add_u32_e32 v31, 1, v27
	s_nop 0
	v_cndmask_b32_e64 v30, v27, v30, s[6:7]
	v_fma_f32 v27, -v31, v27, v26
	v_cmp_lt_f32_e64 s[6:7], 0, v27
	s_nop 1
	v_cndmask_b32_e64 v27, v30, v31, s[6:7]
	v_mul_f32_e32 v30, 0x37800000, v27
	v_cndmask_b32_e32 v27, v27, v30, vcc
	v_cmp_class_f32_e32 vcc, v26, v253
	s_nop 1
	v_cndmask_b32_e32 v26, v27, v26, vcc
	v_div_scale_f32 v27, s[6:7], v26, v26, 1.0
	v_rcp_f32_e32 v30, v27
	s_nop 0
	v_fma_f32 v31, -v27, v30, 1.0
	v_fmac_f32_e32 v30, v31, v30
	v_div_scale_f32 v31, vcc, 1.0, v26, 1.0
	v_mul_f32_e32 v34, v31, v30
	v_fma_f32 v35, -v27, v34, v31
	v_fmac_f32_e32 v34, v35, v30
	v_fma_f32 v27, -v27, v34, v31
	v_div_fmas_f32 v27, v27, v30, v34
	v_div_fixup_f32 v26, v27, v26, 1.0
	v_lshlrev_b32_e32 v30, 16, v22
	v_and_b32_e32 v31, 0xffff0000, v22
	v_lshlrev_b32_e32 v22, 16, v23
	v_and_b32_e32 v23, 0xffff0000, v23
	v_mul_f32_e32 v34, v78, v26
	v_mul_f32_e32 v35, v79, v26
	v_mul_f32_e32 v27, v77, v26
	v_mul_f32_e32 v26, v76, v26
	s_nop 0
	v_mul_f32_e32 v22, v26, v22
	v_mul_f32_e32 v23, v27, v23
	v_mul_f32_e32 v26, v34, v30
	v_mul_f32_e32 v27, v35, v31
	s_nop 0
	v_cvt_pk_bf16_f32 v26, v26, v27
	v_cvt_pk_bf16_f32 v27, v22, v23
	v_add_f32_dpp v22, v147, v147 quad_perm:[1,0,3,2] row_mask:0xf bank_mask:0xf bound_ctrl:1
	global_store_dwordx2 v[44:45], v[26:27], off offset:1536
	s_nop 0
	v_add_f32_dpp v22, v22, v22 quad_perm:[2,3,0,1] row_mask:0xf bank_mask:0xf bound_ctrl:1
	s_nop 1
	v_add_f32_dpp v22, v22, v22 row_half_mirror row_mask:0xf bank_mask:0xf bound_ctrl:1
	s_nop 1
	v_add_f32_dpp v22, v22, v22 row_mirror row_mask:0xf bank_mask:0xf bound_ctrl:1
	s_nop 0
	v_readlane_b32 s9, v22, 16
	v_readlane_b32 s12, v22, 48
	v_readlane_b32 s6, v22, 0
	v_readlane_b32 s7, v22, 32
	v_mov_b32_e32 v22, s9
	v_mov_b32_e32 v23, s12
	v_add_f32_e32 v22, s6, v22
	v_add_f32_e32 v23, s7, v23
	s_nop 0
	v_add_f32_e32 v22, v22, v23
	v_fmamk_f32 v22, v22, 0x3b800000, v252
	v_cmp_gt_f32_e32 vcc, s55, v22
	v_mul_f32_e32 v23, 0x4f800000, v22
	s_nop 0
	v_cndmask_b32_e32 v22, v22, v23, vcc
	v_sqrt_f32_e32 v23, v22
	s_nop 0
	v_add_u32_e32 v26, -1, v23
	v_fma_f32 v27, -v26, v23, v22
	v_cmp_ge_f32_e64 s[6:7], 0, v27
	v_add_u32_e32 v27, 1, v23
	s_nop 0
	v_cndmask_b32_e64 v26, v23, v26, s[6:7]
	v_fma_f32 v23, -v27, v23, v22
	v_cmp_lt_f32_e64 s[6:7], 0, v23
	s_nop 1
	v_cndmask_b32_e64 v23, v26, v27, s[6:7]
	v_mul_f32_e32 v26, 0x37800000, v23
	v_cndmask_b32_e32 v23, v23, v26, vcc
	v_cmp_class_f32_e32 vcc, v22, v253
	s_nop 1
	v_cndmask_b32_e32 v22, v23, v22, vcc
	v_div_scale_f32 v23, s[6:7], v22, v22, 1.0
	v_rcp_f32_e32 v26, v23
	s_nop 0
	v_fma_f32 v27, -v23, v26, 1.0
	v_fmac_f32_e32 v26, v27, v26
	v_div_scale_f32 v27, vcc, 1.0, v22, 1.0
	v_mul_f32_e32 v30, v27, v26
	v_fma_f32 v31, -v23, v30, v27
	v_fmac_f32_e32 v30, v31, v26
	v_fma_f32 v23, -v23, v30, v27
	v_div_fmas_f32 v23, v23, v26, v30
	v_div_fixup_f32 v22, v23, v22, 1.0
	v_lshlrev_b32_e32 v26, 16, v18
	v_and_b32_e32 v27, 0xffff0000, v18
	v_lshlrev_b32_e32 v18, 16, v19
	v_and_b32_e32 v19, 0xffff0000, v19
	v_mul_f32_e32 v30, v74, v22
	v_mul_f32_e32 v31, v75, v22
	v_mul_f32_e32 v23, v73, v22
	v_mul_f32_e32 v22, v72, v22
	s_nop 0
	v_mul_f32_e32 v18, v22, v18
	v_mul_f32_e32 v19, v23, v19
	v_mul_f32_e32 v22, v30, v26
	v_mul_f32_e32 v23, v31, v27
	s_nop 0
	v_cvt_pk_bf16_f32 v22, v22, v23
	v_cvt_pk_bf16_f32 v23, v18, v19
	v_add_f32_dpp v18, v146, v146 quad_perm:[1,0,3,2] row_mask:0xf bank_mask:0xf bound_ctrl:1
	global_store_dwordx2 v[44:45], v[22:23], off offset:2048
	s_nop 0
	v_add_f32_dpp v18, v18, v18 quad_perm:[2,3,0,1] row_mask:0xf bank_mask:0xf bound_ctrl:1
	s_nop 1
	v_add_f32_dpp v18, v18, v18 row_half_mirror row_mask:0xf bank_mask:0xf bound_ctrl:1
	s_nop 1
	v_add_f32_dpp v18, v18, v18 row_mirror row_mask:0xf bank_mask:0xf bound_ctrl:1
	s_nop 0
	v_readlane_b32 s9, v18, 16
	v_readlane_b32 s12, v18, 48
	v_readlane_b32 s6, v18, 0
	v_readlane_b32 s7, v18, 32
	v_mov_b32_e32 v18, s9
	v_mov_b32_e32 v19, s12
	v_add_f32_e32 v18, s6, v18
	v_add_f32_e32 v19, s7, v19
	s_nop 0
	v_add_f32_e32 v18, v18, v19
	v_fmamk_f32 v18, v18, 0x3b800000, v252
	v_cmp_gt_f32_e32 vcc, s55, v18
	v_mul_f32_e32 v19, 0x4f800000, v18
	s_nop 0
	v_cndmask_b32_e32 v18, v18, v19, vcc
	v_sqrt_f32_e32 v19, v18
	s_nop 0
	v_add_u32_e32 v22, -1, v19
	v_fma_f32 v23, -v22, v19, v18
	v_cmp_ge_f32_e64 s[6:7], 0, v23
	v_add_u32_e32 v23, 1, v19
	s_nop 0
	v_cndmask_b32_e64 v22, v19, v22, s[6:7]
	v_fma_f32 v19, -v23, v19, v18
	v_cmp_lt_f32_e64 s[6:7], 0, v19
	s_nop 1
	v_cndmask_b32_e64 v19, v22, v23, s[6:7]
	v_mul_f32_e32 v22, 0x37800000, v19
	v_cndmask_b32_e32 v19, v19, v22, vcc
	v_cmp_class_f32_e32 vcc, v18, v253
	s_nop 1
	v_cndmask_b32_e32 v18, v19, v18, vcc
	v_div_scale_f32 v19, s[6:7], v18, v18, 1.0
	v_rcp_f32_e32 v22, v19
	s_nop 0
	v_fma_f32 v23, -v19, v22, 1.0
	v_fmac_f32_e32 v22, v23, v22
	v_div_scale_f32 v23, vcc, 1.0, v18, 1.0
	v_mul_f32_e32 v26, v23, v22
	v_fma_f32 v27, -v19, v26, v23
	v_fmac_f32_e32 v26, v27, v22
	v_fma_f32 v19, -v19, v26, v23
	v_div_fmas_f32 v19, v19, v22, v26
	v_div_fixup_f32 v18, v19, v18, 1.0
	v_lshlrev_b32_e32 v22, 16, v14
	v_and_b32_e32 v23, 0xffff0000, v14
	v_lshlrev_b32_e32 v14, 16, v15
	v_and_b32_e32 v15, 0xffff0000, v15
	v_mul_f32_e32 v26, v70, v18
	v_mul_f32_e32 v27, v71, v18
	v_mul_f32_e32 v19, v69, v18
	v_mul_f32_e32 v18, v68, v18
	s_nop 0
	v_mul_f32_e32 v14, v18, v14
	v_mul_f32_e32 v15, v19, v15
	v_mul_f32_e32 v18, v26, v22
	v_mul_f32_e32 v19, v27, v23
	s_nop 0
	v_cvt_pk_bf16_f32 v18, v18, v19
	v_cvt_pk_bf16_f32 v19, v14, v15
	v_add_f32_dpp v14, v141, v141 quad_perm:[1,0,3,2] row_mask:0xf bank_mask:0xf bound_ctrl:1
	global_store_dwordx2 v[44:45], v[18:19], off offset:2560
	s_nop 0
; #define GAS __attribute__((address_space(1)))
; #define LAS __attribute__((address_space(3)))
; template <bool HG>
; __device__ __forceinline__ void readout_phase2(const Args& a, Frame& F, const float* gain, int nrows) {
;     ...
;     RO_LOAD(f0, b0, g0, nw); RO_LOAD(f1, b1, g1, nw + 2048); RO_LOAD(f2, b2, g2, nw + 2 * 2048);
;     if (HG) { for (int q = F.tid; q < D / 4; q += NWAVES * 64) ((LAS f32x4*)GL)[q] = ((const GAS f32x4*)gain)[q];
;               asm volatile("s_waitcnt lgkmcnt(0)" ::: "memory"); __builtin_amdgcn_s_barrier(); asm volatile("" ::: "memory"); }
;     RO_FINISH(f0, b0, g0, nw);            RO_LOAD(f0, b0, g0, nw + 3 * 2048);
;     RO_FINISH(f1, b1, g1, nw + 2048);     RO_LOAD(f1, b1, g1, nw + 4 * 2048);
;     RO_FINISH(f2, b2, g2, nw + 2 * 2048); RO_LOAD(f2, b2, g2, nw + 5 * 2048);
;     RO_FINISH(f0, b0, g0, nw + 3 * 2048); RO_LOAD(f0, b0, g0, nw + 6 * 2048);
;     RO_FINISH(f1, b1, g1, nw + 4 * 2048); RO_LOAD(f1, b1, g1, nw + 7 * 2048);
;     RO_FINISH(f2, b2, g2, nw + 5 * 2048);
;     const bool cx = ML + nw < nrows;
;     RO_LOAD(f2, b2, g2, cx ? ML + nw : nw + 7 * 2048);
	v_add_f32_dpp v14, v14, v14 quad_perm:[2,3,0,1] row_mask:0xf bank_mask:0xf bound_ctrl:1
	s_nop 1
	v_add_f32_dpp v14, v14, v14 row_half_mirror row_mask:0xf bank_mask:0xf bound_ctrl:1
	s_nop 1
	v_add_f32_dpp v14, v14, v14 row_mirror row_mask:0xf bank_mask:0xf bound_ctrl:1
	s_nop 0
	v_readlane_b32 s9, v14, 16
	v_readlane_b32 s12, v14, 48
	v_readlane_b32 s6, v14, 0
	v_readlane_b32 s7, v14, 32
	v_mov_b32_e32 v14, s9
	v_mov_b32_e32 v15, s12
	v_add_f32_e32 v14, s6, v14
	v_add_f32_e32 v15, s7, v15
	s_nop 0
	v_add_f32_e32 v14, v14, v15
	v_fmamk_f32 v14, v14, 0x3b800000, v252
	v_cmp_gt_f32_e32 vcc, s55, v14
	v_mul_f32_e32 v15, 0x4f800000, v14
	s_nop 0
	v_cndmask_b32_e32 v14, v14, v15, vcc
	v_sqrt_f32_e32 v15, v14
	s_nop 0
	v_add_u32_e32 v18, -1, v15
	v_fma_f32 v19, -v18, v15, v14
	v_cmp_ge_f32_e64 s[6:7], 0, v19
	v_add_u32_e32 v19, 1, v15
	s_nop 0
	v_cndmask_b32_e64 v18, v15, v18, s[6:7]
	v_fma_f32 v15, -v19, v15, v14
	v_cmp_lt_f32_e64 s[6:7], 0, v15
	s_nop 1
	v_cndmask_b32_e64 v15, v18, v19, s[6:7]
	v_mul_f32_e32 v18, 0x37800000, v15
	v_cndmask_b32_e32 v15, v15, v18, vcc
	v_cmp_class_f32_e32 vcc, v14, v253
	s_nop 1
	v_cndmask_b32_e32 v14, v15, v14, vcc
	v_div_scale_f32 v15, s[6:7], v14, v14, 1.0
	v_rcp_f32_e32 v18, v15
	s_nop 0
	v_fma_f32 v19, -v15, v18, 1.0
	v_fmac_f32_e32 v18, v19, v18
	v_div_scale_f32 v19, vcc, 1.0, v14, 1.0
	v_mul_f32_e32 v22, v19, v18
	v_fma_f32 v23, -v15, v22, v19
	v_fmac_f32_e32 v22, v23, v18
	v_fma_f32 v15, -v15, v22, v19
	v_div_fmas_f32 v15, v15, v18, v22
	v_div_fixup_f32 v14, v15, v14, 1.0
	v_lshlrev_b32_e32 v18, 16, v12
	v_and_b32_e32 v19, 0xffff0000, v12
	v_lshlrev_b32_e32 v12, 16, v13
	v_and_b32_e32 v13, 0xffff0000, v13
	v_mul_f32_e32 v22, v62, v14
	v_mul_f32_e32 v23, v63, v14
	v_mul_f32_e32 v15, v57, v14
	v_mul_f32_e32 v14, v56, v14
	s_nop 0
	v_mul_f32_e32 v12, v14, v12
	v_mul_f32_e32 v13, v15, v13
	v_mul_f32_e32 v14, v22, v18
	v_mul_f32_e32 v15, v23, v19
	s_nop 0
	v_cvt_pk_bf16_f32 v14, v14, v15
	v_cvt_pk_bf16_f32 v15, v12, v13
	v_add_f32_dpp v12, v140, v140 quad_perm:[1,0,3,2] row_mask:0xf bank_mask:0xf bound_ctrl:1
	global_store_dwordx2 v[44:45], v[14:15], off offset:3072
	s_nop 0
	v_add_f32_dpp v12, v12, v12 quad_perm:[2,3,0,1] row_mask:0xf bank_mask:0xf bound_ctrl:1
	s_nop 1
	v_add_f32_dpp v12, v12, v12 row_half_mirror row_mask:0xf bank_mask:0xf bound_ctrl:1
	s_nop 1
	v_add_f32_dpp v12, v12, v12 row_mirror row_mask:0xf bank_mask:0xf bound_ctrl:1
	s_nop 0
	v_readlane_b32 s9, v12, 16
	v_readlane_b32 s12, v12, 48
	v_readlane_b32 s6, v12, 0
	v_readlane_b32 s7, v12, 32
	v_mov_b32_e32 v12, s9
	v_mov_b32_e32 v13, s12
	v_add_f32_e32 v12, s6, v12
	v_add_f32_e32 v13, s7, v13
	s_add_u32 s12, s10, 0x2800000
	v_add_f32_e32 v12, v12, v13
	v_fmamk_f32 v12, v12, 0x3b800000, v252
	v_cmp_gt_f32_e32 vcc, s55, v12
	v_mul_f32_e32 v13, 0x4f800000, v12
	s_addc_u32 s13, s11, 0
	v_cndmask_b32_e32 v12, v12, v13, vcc
	v_sqrt_f32_e32 v13, v12
	s_add_u32 s40, s10, 0x3000000
	s_addc_u32 s41, s11, 0
	s_add_i32 s82, s8, 0x4000
	v_add_u32_e32 v14, -1, v13
	v_fma_f32 v15, -v14, v13, v12
	v_cmp_ge_f32_e64 s[6:7], 0, v15
	v_add_u32_e32 v15, 1, v13
	s_nop 0
	v_cndmask_b32_e64 v14, v13, v14, s[6:7]
	v_fma_f32 v13, -v15, v13, v12
	v_cmp_lt_f32_e64 s[6:7], 0, v13
	s_nop 1
	v_cndmask_b32_e64 v13, v14, v15, s[6:7]
	v_mul_f32_e32 v14, 0x37800000, v13
	v_cndmask_b32_e32 v13, v13, v14, vcc
	v_cmp_class_f32_e32 vcc, v12, v253
	s_nop 1
	v_cndmask_b32_e32 v12, v13, v12, vcc
	v_div_scale_f32 v13, s[6:7], v12, v12, 1.0
	v_rcp_f32_e32 v14, v13
	s_nop 0
	v_fma_f32 v15, -v13, v14, 1.0
	v_fmac_f32_e32 v14, v15, v14
	v_div_scale_f32 v15, vcc, 1.0, v12, 1.0
	v_mul_f32_e32 v18, v15, v14
	v_fma_f32 v19, -v13, v18, v15
	v_fmac_f32_e32 v18, v19, v14
	v_fma_f32 v13, -v13, v18, v15
	v_div_fmas_f32 v13, v13, v14, v18
	v_div_fixup_f32 v12, v13, v12, 1.0
	s_waitcnt vmcnt(62)
	v_lshlrev_b32_e32 v14, 16, v10
	v_and_b32_e32 v15, 0xffff0000, v10
	v_lshlrev_b32_e32 v10, 16, v11
	v_and_b32_e32 v11, 0xffff0000, v11
	v_mul_f32_e32 v18, v50, v12
	v_mul_f32_e32 v19, v51, v12
	v_mul_f32_e32 v13, v39, v12
	v_mul_f32_e32 v12, v38, v12
	s_nop 0
	v_mul_f32_e32 v10, v12, v10
	v_mul_f32_e32 v11, v13, v11
	v_mul_f32_e32 v12, v18, v14
	v_mul_f32_e32 v13, v19, v15
	v_lshl_add_u64 v[14:15], v[8:9], 0, s[12:13]
	v_cvt_pk_bf16_f32 v12, v12, v13
	v_cvt_pk_bf16_f32 v13, v10, v11
	global_store_dwordx2 v[44:45], v[12:13], off offset:3584
	v_lshl_add_u64 v[10:11], v[4:5], 0, s[12:13]
	v_lshl_add_u64 v[12:13], v[6:7], 0, s[12:13]
	v_lshl_add_u64 v[10:11], v[10:11], 0, v[0:1]
	v_lshl_add_u64 v[12:13], v[12:13], 0, v[0:1]
	v_lshl_add_u64 v[14:15], v[14:15], 0, v[0:1]
	global_load_dwordx2 v[158:159], v[10:11], off nt
	global_load_dwordx2 v[152:153], v[12:13], off nt
	global_load_dwordx2 v[62:63], v[14:15], off nt
	global_load_dwordx2 v[146:147], v[10:11], off offset:512 nt
	global_load_dwordx2 v[140:141], v[12:13], off offset:512 nt
	global_load_dwordx2 v[56:57], v[14:15], off offset:512 nt
	global_load_dwordx2 v[134:135], v[10:11], off offset:1024 nt
	global_load_dwordx2 v[88:89], v[12:13], off offset:1024 nt
	global_load_dwordx2 v[50:51], v[14:15], off offset:1024 nt
	global_load_dwordx2 v[84:85], v[10:11], off offset:1536 nt
	global_load_dwordx2 v[86:87], v[12:13], off offset:1536 nt
	global_load_dwordx2 v[44:45], v[14:15], off offset:1536 nt
	global_load_dwordx2 v[82:83], v[10:11], off offset:2048 nt
	global_load_dwordx2 v[80:81], v[12:13], off offset:2048 nt
	global_load_dwordx2 v[38:39], v[14:15], off offset:2048 nt
	global_load_dwordx2 v[78:79], v[10:11], off offset:2560 nt
	global_load_dwordx2 v[76:77], v[12:13], off offset:2560 nt
	global_load_dwordx2 v[34:35], v[14:15], off offset:2560 nt
	global_load_dwordx2 v[74:75], v[10:11], off offset:3072 nt
	global_load_dwordx2 v[72:73], v[12:13], off offset:3072 nt
	global_load_dwordx2 v[30:31], v[14:15], off offset:3072 nt
	global_load_dwordx2 v[68:69], v[10:11], off offset:3584 nt
	global_load_dwordx2 v[70:71], v[12:13], off offset:3584 nt
	global_load_dwordx2 v[26:27], v[14:15], off offset:3584 nt
	v_lshlrev_b32_e32 v10, 16, v160
	v_and_b32_e32 v11, 0xffff0000, v160
	s_waitcnt vmcnt(62)
	v_lshlrev_b32_e32 v12, 16, v154
	v_and_b32_e32 v13, 0xffff0000, v154
	v_add_f32_e32 v164, v10, v12
	v_add_f32_e32 v165, v11, v13
	v_lshlrev_b32_e32 v10, 16, v161
	v_and_b32_e32 v11, 0xffff0000, v161
	v_lshlrev_b32_e32 v12, 16, v155
	v_and_b32_e32 v13, 0xffff0000, v155
	v_add_f32_e32 v160, v10, v12
	v_add_f32_e32 v161, v11, v13
	v_mov_b32_e32 v12, v165
	v_mov_b32_e32 v13, v161
	v_mov_b32_e32 v10, v164
	v_mov_b32_e32 v11, v160
	v_mul_f32_e32 v12, v12, v12
	v_mul_f32_e32 v13, v13, v13
	v_lshlrev_b32_e32 v14, 16, v95
	v_fma_f32 v10, v10, v10, v12
	v_fma_f32 v11, v11, v11, v13
	v_lshlrev_b32_e32 v12, 16, v142
	v_add_f32_e32 v167, v10, v11
	v_lshlrev_b32_e32 v10, 16, v148
	v_and_b32_e32 v11, 0xffff0000, v148
	v_and_b32_e32 v13, 0xffff0000, v142
	v_add_f32_e32 v154, v10, v12
	v_add_f32_e32 v155, v11, v13
	v_lshlrev_b32_e32 v10, 16, v149
	v_and_b32_e32 v11, 0xffff0000, v149
	v_lshlrev_b32_e32 v12, 16, v143
	v_and_b32_e32 v13, 0xffff0000, v143
	v_add_f32_e32 v148, v10, v12
	v_add_f32_e32 v149, v11, v13
	v_mov_b32_e32 v12, v155
	v_mov_b32_e32 v13, v149
	v_mov_b32_e32 v10, v154
	v_mov_b32_e32 v11, v148
	v_mul_f32_e32 v12, v12, v12
	v_mul_f32_e32 v13, v13, v13
	v_and_b32_e32 v15, 0xffff0000, v95
	v_fma_f32 v10, v10, v10, v12
	v_fma_f32 v11, v11, v11, v13
	v_lshlrev_b32_e32 v12, 16, v130
	v_add_f32_e32 v168, v10, v11
	v_lshlrev_b32_e32 v10, 16, v136
	v_and_b32_e32 v11, 0xffff0000, v136
	v_and_b32_e32 v13, 0xffff0000, v130
	v_add_f32_e32 v142, v10, v12
	v_add_f32_e32 v143, v11, v13
	v_lshlrev_b32_e32 v10, 16, v137
	v_and_b32_e32 v11, 0xffff0000, v137
	v_lshlrev_b32_e32 v12, 16, v131
	v_and_b32_e32 v13, 0xffff0000, v131
	v_add_f32_e32 v136, v10, v12
	v_add_f32_e32 v137, v11, v13
	v_mov_b32_e32 v12, v143
	v_mov_b32_e32 v13, v137
	v_mov_b32_e32 v10, v142
	v_mov_b32_e32 v11, v136
	v_mul_f32_e32 v12, v12, v12
	v_mul_f32_e32 v13, v13, v13
	s_nop 0
	v_fma_f32 v10, v10, v10, v12
	v_fma_f32 v11, v11, v11, v13
	v_lshlrev_b32_e32 v12, 16, v126
	v_add_f32_e32 v169, v10, v11
	v_lshlrev_b32_e32 v10, 16, v122
	v_and_b32_e32 v11, 0xffff0000, v122
	v_and_b32_e32 v13, 0xffff0000, v126
	v_add_f32_e32 v130, v10, v12
	v_add_f32_e32 v131, v11, v13
	v_lshlrev_b32_e32 v10, 16, v123
	v_and_b32_e32 v11, 0xffff0000, v123
	v_lshlrev_b32_e32 v12, 16, v127
	v_and_b32_e32 v13, 0xffff0000, v127
	v_add_f32_e32 v126, v10, v12
	v_add_f32_e32 v127, v11, v13
	v_mov_b32_e32 v12, v131
	v_mov_b32_e32 v13, v127
	v_mov_b32_e32 v10, v130
	v_mov_b32_e32 v11, v126
	v_mul_f32_e32 v12, v12, v12
	v_mul_f32_e32 v13, v13, v13
	s_nop 0
	v_fma_f32 v10, v10, v10, v12
	v_fma_f32 v11, v11, v11, v13
	v_lshlrev_b32_e32 v12, 16, v114
	v_add_f32_e32 v170, v10, v11
	v_lshlrev_b32_e32 v10, 16, v118
	v_and_b32_e32 v11, 0xffff0000, v118
	v_and_b32_e32 v13, 0xffff0000, v114
	v_add_f32_e32 v122, v10, v12
	v_add_f32_e32 v123, v11, v13
	v_lshlrev_b32_e32 v10, 16, v119
	v_and_b32_e32 v11, 0xffff0000, v119
	v_lshlrev_b32_e32 v12, 16, v115
	v_and_b32_e32 v13, 0xffff0000, v115
	v_add_f32_e32 v118, v10, v12
	v_add_f32_e32 v119, v11, v13
	v_mov_b32_e32 v12, v123
	v_mov_b32_e32 v13, v119
	v_mov_b32_e32 v10, v122
	v_mov_b32_e32 v11, v118
	v_mul_f32_e32 v12, v12, v12
	v_mul_f32_e32 v13, v13, v13
	s_nop 0
	v_fma_f32 v10, v10, v10, v12
	v_fma_f32 v11, v11, v11, v13
	v_lshlrev_b32_e32 v12, 16, v106
	v_add_f32_e32 v166, v10, v11
	v_lshlrev_b32_e32 v10, 16, v110
	v_and_b32_e32 v11, 0xffff0000, v110
	v_and_b32_e32 v13, 0xffff0000, v106
	v_add_f32_e32 v114, v10, v12
	v_add_f32_e32 v115, v11, v13
	v_lshlrev_b32_e32 v10, 16, v111
	v_and_b32_e32 v11, 0xffff0000, v111
	v_lshlrev_b32_e32 v12, 16, v107
	v_and_b32_e32 v13, 0xffff0000, v107
	v_add_f32_e32 v106, v10, v12
	v_add_f32_e32 v107, v11, v13
	v_mov_b32_e32 v12, v115
	v_mov_b32_e32 v13, v107
	v_mov_b32_e32 v10, v114
	v_mov_b32_e32 v11, v106
	v_mul_f32_e32 v12, v12, v12
	v_mul_f32_e32 v13, v13, v13
	s_nop 0
	v_fma_f32 v10, v10, v10, v12
	v_fma_f32 v11, v11, v11, v13
	v_lshlrev_b32_e32 v12, 16, v98
	v_add_f32_e32 v110, v10, v11
	v_lshlrev_b32_e32 v10, 16, v102
	v_and_b32_e32 v11, 0xffff0000, v102
	v_and_b32_e32 v13, 0xffff0000, v98
	v_add_f32_e32 v18, v10, v12
	v_add_f32_e32 v19, v11, v13
	v_lshlrev_b32_e32 v10, 16, v103
	v_and_b32_e32 v11, 0xffff0000, v103
	v_lshlrev_b32_e32 v12, 16, v99
	v_and_b32_e32 v13, 0xffff0000, v99
	v_add_f32_e32 v22, v10, v12
	v_add_f32_e32 v23, v11, v13
	v_mov_b32_e32 v12, v19
	v_mov_b32_e32 v13, v23
	v_mov_b32_e32 v10, v18
	v_mov_b32_e32 v11, v22
	v_mul_f32_e32 v12, v12, v12
	v_mul_f32_e32 v13, v13, v13
	s_nop 0
	v_fma_f32 v10, v10, v10, v12
	v_fma_f32 v11, v11, v11, v13
	v_lshlrev_b32_e32 v12, 16, v94
	v_add_f32_e32 v98, v10, v11
	v_lshlrev_b32_e32 v10, 16, v90
	v_and_b32_e32 v11, 0xffff0000, v90
	v_and_b32_e32 v13, 0xffff0000, v94
	v_add_f32_e32 v10, v10, v12
	v_add_f32_e32 v11, v11, v13
	v_lshlrev_b32_e32 v12, 16, v91
	v_and_b32_e32 v13, 0xffff0000, v91
	v_add_f32_e32 v12, v12, v14
	v_add_f32_e32 v13, v13, v15
	v_mov_b32_e32 v90, v11
	v_mov_b32_e32 v91, v13
	v_mov_b32_e32 v14, v10
	v_mov_b32_e32 v15, v12
	v_mul_f32_e32 v90, v90, v90
	v_mul_f32_e32 v91, v91, v91
	s_nop 0
	v_fma_f32 v14, v14, v14, v90
	v_fma_f32 v15, v15, v15, v91
	v_add_f32_dpp v91, v167, v167 quad_perm:[1,0,3,2] row_mask:0xf bank_mask:0xf bound_ctrl:1
	v_add_f32_e32 v90, v14, v15
	v_lshl_add_u64 v[14:15], v[2:3], 0, s[14:15]
	v_add_f32_dpp v91, v91, v91 quad_perm:[2,3,0,1] row_mask:0xf bank_mask:0xf bound_ctrl:1
	v_lshl_add_u64 v[14:15], v[14:15], 0, v[0:1]
	s_nop 0
	v_add_f32_dpp v91, v91, v91 row_half_mirror row_mask:0xf bank_mask:0xf bound_ctrl:1
	s_nop 1
	v_add_f32_dpp v91, v91, v91 row_mirror row_mask:0xf bank_mask:0xf bound_ctrl:1
	s_nop 0
	v_readlane_b32 s9, v91, 16
	v_readlane_b32 s14, v91, 48
	v_readlane_b32 s6, v91, 0
	v_readlane_b32 s7, v91, 32
	v_mov_b32_e32 v94, s9
	v_mov_b32_e32 v95, s14
	v_add_f32_e32 v94, s6, v94
	v_add_f32_e32 v95, s7, v95
	s_nop 0
	v_add_f32_e32 v91, v94, v95
	v_fmamk_f32 v91, v91, 0x3b800000, v252
	v_cmp_gt_f32_e32 vcc, s55, v91
	v_mul_f32_e32 v94, 0x4f800000, v91
	s_nop 0
	v_cndmask_b32_e32 v91, v91, v94, vcc
	v_sqrt_f32_e32 v94, v91
	s_nop 0
	v_add_u32_e32 v95, -1, v94
	v_fma_f32 v99, -v95, v94, v91
	v_cmp_ge_f32_e64 s[6:7], 0, v99
	v_add_u32_e32 v99, 1, v94
	s_nop 0
	v_cndmask_b32_e64 v95, v94, v95, s[6:7]
	v_fma_f32 v94, -v99, v94, v91
	v_cmp_lt_f32_e64 s[6:7], 0, v94
	s_nop 1
	v_cndmask_b32_e64 v94, v95, v99, s[6:7]
	v_mul_f32_e32 v95, 0x37800000, v94
	v_cndmask_b32_e32 v94, v94, v95, vcc
	v_cmp_class_f32_e32 vcc, v91, v253
	s_nop 1
	v_cndmask_b32_e32 v91, v94, v91, vcc
	v_div_scale_f32 v94, s[6:7], v91, v91, 1.0
	v_rcp_f32_e32 v95, v94
	s_nop 0
	v_fma_f32 v99, -v94, v95, 1.0
	v_fmac_f32_e32 v95, v99, v95
	v_div_scale_f32 v99, vcc, 1.0, v91, 1.0
	v_mul_f32_e32 v102, v99, v95
	v_fma_f32 v103, -v94, v102, v99
	v_fmac_f32_e32 v102, v103, v95
	v_fma_f32 v94, -v94, v102, v99
	v_div_fmas_f32 v94, v94, v95, v102
	v_div_fixup_f32 v94, v94, v91, 1.0
	v_lshlrev_b32_e32 v102, 16, v64
	v_and_b32_e32 v103, 0xffff0000, v64
	v_lshlrev_b32_e32 v64, 16, v65
	v_and_b32_e32 v65, 0xffff0000, v65
	v_mul_f32_e32 v164, v164, v94
	v_mul_f32_e32 v165, v165, v94
	v_mul_f32_e32 v95, v161, v94
	v_mul_f32_e32 v94, v160, v94
	s_nop 0
	v_mul_f32_e32 v64, v94, v64
	v_mul_f32_e32 v65, v95, v65
	v_mul_f32_e32 v94, v164, v102
	v_mul_f32_e32 v95, v165, v103
	s_nop 0
	v_cvt_pk_bf16_f32 v94, v94, v95
	v_cvt_pk_bf16_f32 v95, v64, v65
	v_add_f32_dpp v64, v168, v168 quad_perm:[1,0,3,2] row_mask:0xf bank_mask:0xf bound_ctrl:1
	global_store_dwordx2 v[14:15], v[94:95], off
	s_nop 0
	v_add_f32_dpp v64, v64, v64 quad_perm:[2,3,0,1] row_mask:0xf bank_mask:0xf bound_ctrl:1
	s_nop 1
	v_add_f32_dpp v64, v64, v64 row_half_mirror row_mask:0xf bank_mask:0xf bound_ctrl:1
	s_nop 1
	v_add_f32_dpp v64, v64, v64 row_mirror row_mask:0xf bank_mask:0xf bound_ctrl:1
	s_nop 0
	v_readlane_b32 s9, v64, 16
	v_readlane_b32 s14, v64, 48
	v_readlane_b32 s6, v64, 0
	v_readlane_b32 s7, v64, 32
	v_mov_b32_e32 v64, s9
	v_mov_b32_e32 v65, s14
	v_add_f32_e32 v64, s6, v64
	v_add_f32_e32 v65, s7, v65
	s_nop 0
	v_add_f32_e32 v64, v64, v65
	v_fmamk_f32 v64, v64, 0x3b800000, v252
	v_cmp_gt_f32_e32 vcc, s55, v64
	v_mul_f32_e32 v65, 0x4f800000, v64
	s_nop 0
	v_cndmask_b32_e32 v64, v64, v65, vcc
	v_sqrt_f32_e32 v65, v64
	s_nop 0
	v_add_u32_e32 v91, -1, v65
	v_fma_f32 v94, -v91, v65, v64
	v_cmp_ge_f32_e64 s[6:7], 0, v94
	v_add_u32_e32 v94, 1, v65
	s_nop 0
	v_cndmask_b32_e64 v91, v65, v91, s[6:7]
	v_fma_f32 v65, -v94, v65, v64
	v_cmp_lt_f32_e64 s[6:7], 0, v65
	s_nop 1
	v_cndmask_b32_e64 v65, v91, v94, s[6:7]
	v_mul_f32_e32 v91, 0x37800000, v65
	v_cndmask_b32_e32 v65, v65, v91, vcc
	v_cmp_class_f32_e32 vcc, v64, v253
	s_nop 1
	v_cndmask_b32_e32 v64, v65, v64, vcc
	v_div_scale_f32 v65, s[6:7], v64, v64, 1.0
	v_rcp_f32_e32 v91, v65
	s_nop 0
	v_fma_f32 v94, -v65, v91, 1.0
	v_fmac_f32_e32 v91, v94, v91
	v_div_scale_f32 v94, vcc, 1.0, v64, 1.0
	v_mul_f32_e32 v95, v94, v91
	v_fma_f32 v99, -v65, v95, v94
	v_fmac_f32_e32 v95, v99, v91
	v_fma_f32 v65, -v65, v95, v94
	v_div_fmas_f32 v65, v65, v91, v95
	v_div_fixup_f32 v64, v65, v64, 1.0
	v_lshlrev_b32_e32 v94, 16, v58
	v_and_b32_e32 v95, 0xffff0000, v58
	v_lshlrev_b32_e32 v58, 16, v59
	v_and_b32_e32 v59, 0xffff0000, v59
	v_mul_f32_e32 v102, v154, v64
	v_mul_f32_e32 v103, v155, v64
	v_mul_f32_e32 v65, v149, v64
	v_mul_f32_e32 v64, v148, v64
	s_nop 0
	v_mul_f32_e32 v58, v64, v58
	v_mul_f32_e32 v59, v65, v59
	v_mul_f32_e32 v64, v102, v94
	v_mul_f32_e32 v65, v103, v95
	s_nop 0
	v_cvt_pk_bf16_f32 v64, v64, v65
	v_cvt_pk_bf16_f32 v65, v58, v59
	v_add_f32_dpp v58, v169, v169 quad_perm:[1,0,3,2] row_mask:0xf bank_mask:0xf bound_ctrl:1
	global_store_dwordx2 v[14:15], v[64:65], off offset:512
	s_nop 0
	v_add_f32_dpp v58, v58, v58 quad_perm:[2,3,0,1] row_mask:0xf bank_mask:0xf bound_ctrl:1
	s_nop 1
	v_add_f32_dpp v58, v58, v58 row_half_mirror row_mask:0xf bank_mask:0xf bound_ctrl:1
	s_nop 1
	v_add_f32_dpp v58, v58, v58 row_mirror row_mask:0xf bank_mask:0xf bound_ctrl:1
	s_nop 0
	v_readlane_b32 s9, v58, 16
	v_readlane_b32 s14, v58, 48
	v_readlane_b32 s6, v58, 0
	v_readlane_b32 s7, v58, 32
	v_mov_b32_e32 v58, s9
	v_mov_b32_e32 v59, s14
	v_add_f32_e32 v58, s6, v58
	v_add_f32_e32 v59, s7, v59
	s_nop 0
	v_add_f32_e32 v58, v58, v59
	v_fmamk_f32 v58, v58, 0x3b800000, v252
	v_cmp_gt_f32_e32 vcc, s55, v58
	v_mul_f32_e32 v59, 0x4f800000, v58
	s_nop 0
	v_cndmask_b32_e32 v58, v58, v59, vcc
	v_sqrt_f32_e32 v59, v58
	s_nop 0
	v_add_u32_e32 v64, -1, v59
	v_fma_f32 v65, -v64, v59, v58
	v_cmp_ge_f32_e64 s[6:7], 0, v65
	v_add_u32_e32 v65, 1, v59
	s_nop 0
	v_cndmask_b32_e64 v64, v59, v64, s[6:7]
	v_fma_f32 v59, -v65, v59, v58
	v_cmp_lt_f32_e64 s[6:7], 0, v59
	s_nop 1
	v_cndmask_b32_e64 v59, v64, v65, s[6:7]
	v_mul_f32_e32 v64, 0x37800000, v59
	v_cndmask_b32_e32 v59, v59, v64, vcc
	v_cmp_class_f32_e32 vcc, v58, v253
	s_nop 1
	v_cndmask_b32_e32 v58, v59, v58, vcc
	v_div_scale_f32 v59, s[6:7], v58, v58, 1.0
	v_rcp_f32_e32 v64, v59
	s_nop 0
	v_fma_f32 v65, -v59, v64, 1.0
	v_fmac_f32_e32 v64, v65, v64
	v_div_scale_f32 v65, vcc, 1.0, v58, 1.0
	v_mul_f32_e32 v91, v65, v64
	v_fma_f32 v94, -v59, v91, v65
	v_fmac_f32_e32 v91, v94, v64
	v_fma_f32 v59, -v59, v91, v65
	v_div_fmas_f32 v59, v59, v64, v91
	v_div_fixup_f32 v58, v59, v58, 1.0
	v_lshlrev_b32_e32 v64, 16, v52
	v_and_b32_e32 v65, 0xffff0000, v52
	v_lshlrev_b32_e32 v52, 16, v53
	v_and_b32_e32 v53, 0xffff0000, v53
	v_mul_f32_e32 v94, v142, v58
	v_mul_f32_e32 v95, v143, v58
	v_mul_f32_e32 v59, v137, v58
	v_mul_f32_e32 v58, v136, v58
	s_nop 0
	v_mul_f32_e32 v52, v58, v52
	v_mul_f32_e32 v53, v59, v53
	v_mul_f32_e32 v58, v94, v64
	v_mul_f32_e32 v59, v95, v65
	s_nop 0
	v_cvt_pk_bf16_f32 v58, v58, v59
	v_cvt_pk_bf16_f32 v59, v52, v53
	v_add_f32_dpp v52, v170, v170 quad_perm:[1,0,3,2] row_mask:0xf bank_mask:0xf bound_ctrl:1
	global_store_dwordx2 v[14:15], v[58:59], off offset:1024
	s_nop 0
	v_add_f32_dpp v52, v52, v52 quad_perm:[2,3,0,1] row_mask:0xf bank_mask:0xf bound_ctrl:1
	s_nop 1
	v_add_f32_dpp v52, v52, v52 row_half_mirror row_mask:0xf bank_mask:0xf bound_ctrl:1
	s_nop 1
	v_add_f32_dpp v52, v52, v52 row_mirror row_mask:0xf bank_mask:0xf bound_ctrl:1
	s_nop 0
	v_readlane_b32 s9, v52, 16
	v_readlane_b32 s14, v52, 48
	v_readlane_b32 s6, v52, 0
	v_readlane_b32 s7, v52, 32
	v_mov_b32_e32 v52, s9
	v_mov_b32_e32 v53, s14
	v_add_f32_e32 v52, s6, v52
	v_add_f32_e32 v53, s7, v53
	s_nop 0
	v_add_f32_e32 v52, v52, v53
	v_fmamk_f32 v52, v52, 0x3b800000, v252
	v_cmp_gt_f32_e32 vcc, s55, v52
	v_mul_f32_e32 v53, 0x4f800000, v52
	s_nop 0
	v_cndmask_b32_e32 v52, v52, v53, vcc
	v_sqrt_f32_e32 v53, v52
	s_nop 0
	v_add_u32_e32 v58, -1, v53
	v_fma_f32 v59, -v58, v53, v52
	v_cmp_ge_f32_e64 s[6:7], 0, v59
	v_add_u32_e32 v59, 1, v53
	s_nop 0
	v_cndmask_b32_e64 v58, v53, v58, s[6:7]
	v_fma_f32 v53, -v59, v53, v52
	v_cmp_lt_f32_e64 s[6:7], 0, v53
	s_nop 1
	v_cndmask_b32_e64 v53, v58, v59, s[6:7]
	v_mul_f32_e32 v58, 0x37800000, v53
	v_cndmask_b32_e32 v53, v53, v58, vcc
	v_cmp_class_f32_e32 vcc, v52, v253
	s_nop 1
	v_cndmask_b32_e32 v52, v53, v52, vcc
	v_div_scale_f32 v53, s[6:7], v52, v52, 1.0
	v_rcp_f32_e32 v58, v53
	s_nop 0
	v_fma_f32 v59, -v53, v58, 1.0
	v_fmac_f32_e32 v58, v59, v58
	v_div_scale_f32 v59, vcc, 1.0, v52, 1.0
	v_mul_f32_e32 v64, v59, v58
	v_fma_f32 v65, -v53, v64, v59
	v_fmac_f32_e32 v64, v65, v58
	v_fma_f32 v53, -v53, v64, v59
	v_div_fmas_f32 v53, v53, v58, v64
	v_div_fixup_f32 v52, v53, v52, 1.0
	v_lshlrev_b32_e32 v58, 16, v46
	v_and_b32_e32 v59, 0xffff0000, v46
	v_lshlrev_b32_e32 v46, 16, v47
	v_and_b32_e32 v47, 0xffff0000, v47
	v_mul_f32_e32 v64, v130, v52
	v_mul_f32_e32 v65, v131, v52
	v_mul_f32_e32 v53, v127, v52
	v_mul_f32_e32 v52, v126, v52
	s_nop 0
	v_mul_f32_e32 v46, v52, v46
	v_mul_f32_e32 v47, v53, v47
	v_mul_f32_e32 v52, v64, v58
	v_mul_f32_e32 v53, v65, v59
	s_nop 0
	v_cvt_pk_bf16_f32 v52, v52, v53
	v_cvt_pk_bf16_f32 v53, v46, v47
	v_add_f32_dpp v46, v166, v166 quad_perm:[1,0,3,2] row_mask:0xf bank_mask:0xf bound_ctrl:1
	global_store_dwordx2 v[14:15], v[52:53], off offset:1536
	s_nop 0
	v_add_f32_dpp v46, v46, v46 quad_perm:[2,3,0,1] row_mask:0xf bank_mask:0xf bound_ctrl:1
	s_nop 1
	v_add_f32_dpp v46, v46, v46 row_half_mirror row_mask:0xf bank_mask:0xf bound_ctrl:1
	s_nop 1
	v_add_f32_dpp v46, v46, v46 row_mirror row_mask:0xf bank_mask:0xf bound_ctrl:1
	s_nop 0
	v_readlane_b32 s9, v46, 16
	v_readlane_b32 s14, v46, 48
	v_readlane_b32 s6, v46, 0
	v_readlane_b32 s7, v46, 32
	v_mov_b32_e32 v46, s9
	v_mov_b32_e32 v47, s14
	v_add_f32_e32 v46, s6, v46
	v_add_f32_e32 v47, s7, v47
	s_nop 0
	v_add_f32_e32 v46, v46, v47
	v_fmamk_f32 v46, v46, 0x3b800000, v252
	v_cmp_gt_f32_e32 vcc, s55, v46
	v_mul_f32_e32 v47, 0x4f800000, v46
	s_nop 0
	v_cndmask_b32_e32 v46, v46, v47, vcc
	v_sqrt_f32_e32 v47, v46
	s_nop 0
	v_add_u32_e32 v52, -1, v47
	v_fma_f32 v53, -v52, v47, v46
	v_cmp_ge_f32_e64 s[6:7], 0, v53
	v_add_u32_e32 v53, 1, v47
	s_nop 0
	v_cndmask_b32_e64 v52, v47, v52, s[6:7]
	v_fma_f32 v47, -v53, v47, v46
	v_cmp_lt_f32_e64 s[6:7], 0, v47
	s_nop 1
	v_cndmask_b32_e64 v47, v52, v53, s[6:7]
	v_mul_f32_e32 v52, 0x37800000, v47
	v_cndmask_b32_e32 v47, v47, v52, vcc
	v_cmp_class_f32_e32 vcc, v46, v253
	s_nop 1
	v_cndmask_b32_e32 v46, v47, v46, vcc
	v_div_scale_f32 v47, s[6:7], v46, v46, 1.0
	v_rcp_f32_e32 v52, v47
	s_nop 0
	v_fma_f32 v53, -v47, v52, 1.0
	v_fmac_f32_e32 v52, v53, v52
	v_div_scale_f32 v53, vcc, 1.0, v46, 1.0
	v_mul_f32_e32 v58, v53, v52
	v_fma_f32 v59, -v47, v58, v53
	v_fmac_f32_e32 v58, v59, v52
	v_fma_f32 v47, -v47, v58, v53
	v_div_fmas_f32 v47, v47, v52, v58
	v_div_fixup_f32 v46, v47, v46, 1.0
	v_lshlrev_b32_e32 v52, 16, v40
	v_and_b32_e32 v53, 0xffff0000, v40
	v_lshlrev_b32_e32 v40, 16, v41
	v_and_b32_e32 v41, 0xffff0000, v41
	v_mul_f32_e32 v58, v122, v46
	v_mul_f32_e32 v59, v123, v46
	v_mul_f32_e32 v47, v119, v46
	v_mul_f32_e32 v46, v118, v46
	s_nop 0
	v_mul_f32_e32 v40, v46, v40
	v_mul_f32_e32 v41, v47, v41
	v_mul_f32_e32 v46, v58, v52
	v_mul_f32_e32 v47, v59, v53
	s_nop 0
	v_cvt_pk_bf16_f32 v46, v46, v47
	v_cvt_pk_bf16_f32 v47, v40, v41
	v_add_f32_dpp v40, v110, v110 quad_perm:[1,0,3,2] row_mask:0xf bank_mask:0xf bound_ctrl:1
	global_store_dwordx2 v[14:15], v[46:47], off offset:2048
	s_nop 0
	v_add_f32_dpp v40, v40, v40 quad_perm:[2,3,0,1] row_mask:0xf bank_mask:0xf bound_ctrl:1
	s_nop 1
	v_add_f32_dpp v40, v40, v40 row_half_mirror row_mask:0xf bank_mask:0xf bound_ctrl:1
	s_nop 1
	v_add_f32_dpp v40, v40, v40 row_mirror row_mask:0xf bank_mask:0xf bound_ctrl:1
	s_nop 0
	v_readlane_b32 s9, v40, 16
	v_readlane_b32 s14, v40, 48
	v_readlane_b32 s6, v40, 0
	v_readlane_b32 s7, v40, 32
	v_mov_b32_e32 v40, s9
	v_mov_b32_e32 v41, s14
	v_add_f32_e32 v40, s6, v40
	v_add_f32_e32 v41, s7, v41
	s_nop 0
	v_add_f32_e32 v40, v40, v41
	v_fmamk_f32 v40, v40, 0x3b800000, v252
	v_cmp_gt_f32_e32 vcc, s55, v40
	v_mul_f32_e32 v41, 0x4f800000, v40
	s_nop 0
	v_cndmask_b32_e32 v40, v40, v41, vcc
	v_sqrt_f32_e32 v41, v40
	s_nop 0
	v_add_u32_e32 v46, -1, v41
	v_fma_f32 v47, -v46, v41, v40
	v_cmp_ge_f32_e64 s[6:7], 0, v47
	v_add_u32_e32 v47, 1, v41
	s_nop 0
	v_cndmask_b32_e64 v46, v41, v46, s[6:7]
	v_fma_f32 v41, -v47, v41, v40
	v_cmp_lt_f32_e64 s[6:7], 0, v41
	s_nop 1
	v_cndmask_b32_e64 v41, v46, v47, s[6:7]
	v_mul_f32_e32 v46, 0x37800000, v41
	v_cndmask_b32_e32 v41, v41, v46, vcc
	v_cmp_class_f32_e32 vcc, v40, v253
	s_nop 1
	v_cndmask_b32_e32 v40, v41, v40, vcc
	v_div_scale_f32 v41, s[6:7], v40, v40, 1.0
	v_rcp_f32_e32 v46, v41
	s_nop 0
	v_fma_f32 v47, -v41, v46, 1.0
	v_fmac_f32_e32 v46, v47, v46
	v_div_scale_f32 v47, vcc, 1.0, v40, 1.0
	v_mul_f32_e32 v52, v47, v46
	v_fma_f32 v53, -v41, v52, v47
	v_fmac_f32_e32 v52, v53, v46
	v_fma_f32 v41, -v41, v52, v47
	v_div_fmas_f32 v41, v41, v46, v52
	v_div_fixup_f32 v40, v41, v40, 1.0
	v_lshlrev_b32_e32 v46, 16, v24
	v_and_b32_e32 v47, 0xffff0000, v24
	v_lshlrev_b32_e32 v24, 16, v25
	v_and_b32_e32 v25, 0xffff0000, v25
	v_mul_f32_e32 v52, v114, v40
	v_mul_f32_e32 v53, v115, v40
	v_mul_f32_e32 v41, v107, v40
	v_mul_f32_e32 v40, v106, v40
	s_nop 0
	v_mul_f32_e32 v24, v40, v24
	v_mul_f32_e32 v25, v41, v25
	v_mul_f32_e32 v40, v52, v46
	v_mul_f32_e32 v41, v53, v47
	s_waitcnt vmcnt(38)
	v_lshlrev_b32_e32 v52, 16, v97
	v_cvt_pk_bf16_f32 v40, v40, v41
	v_cvt_pk_bf16_f32 v41, v24, v25
	v_add_f32_dpp v24, v98, v98 quad_perm:[1,0,3,2] row_mask:0xf bank_mask:0xf bound_ctrl:1
	global_store_dwordx2 v[14:15], v[40:41], off offset:2560
	v_and_b32_e32 v53, 0xffff0000, v97
	v_add_f32_dpp v24, v24, v24 quad_perm:[2,3,0,1] row_mask:0xf bank_mask:0xf bound_ctrl:1
	s_nop 1
	v_add_f32_dpp v24, v24, v24 row_half_mirror row_mask:0xf bank_mask:0xf bound_ctrl:1
	s_nop 1
	v_add_f32_dpp v24, v24, v24 row_mirror row_mask:0xf bank_mask:0xf bound_ctrl:1
	s_nop 0
	v_readlane_b32 s9, v24, 16
	v_readlane_b32 s14, v24, 48
	v_readlane_b32 s6, v24, 0
	v_readlane_b32 s7, v24, 32
	v_mov_b32_e32 v24, s9
	v_mov_b32_e32 v25, s14
	v_add_f32_e32 v24, s6, v24
	v_add_f32_e32 v25, s7, v25
	s_nop 0
	v_add_f32_e32 v24, v24, v25
	v_fmamk_f32 v24, v24, 0x3b800000, v252
	v_cmp_gt_f32_e32 vcc, s55, v24
	v_mul_f32_e32 v25, 0x4f800000, v24
	s_nop 0
	v_cndmask_b32_e32 v24, v24, v25, vcc
	v_sqrt_f32_e32 v25, v24
	s_nop 0
	v_add_u32_e32 v40, -1, v25
	v_fma_f32 v41, -v40, v25, v24
	v_cmp_ge_f32_e64 s[6:7], 0, v41
	v_add_u32_e32 v41, 1, v25
	s_nop 0
	v_cndmask_b32_e64 v40, v25, v40, s[6:7]
	v_fma_f32 v25, -v41, v25, v24
	v_cmp_lt_f32_e64 s[6:7], 0, v25
	s_nop 1
	v_cndmask_b32_e64 v25, v40, v41, s[6:7]
	v_mul_f32_e32 v40, 0x37800000, v25
	v_cndmask_b32_e32 v25, v25, v40, vcc
	v_cmp_class_f32_e32 vcc, v24, v253
	s_nop 1
	v_cndmask_b32_e32 v24, v25, v24, vcc
	v_div_scale_f32 v25, s[6:7], v24, v24, 1.0
	v_rcp_f32_e32 v40, v25
	s_nop 0
	v_fma_f32 v41, -v25, v40, 1.0
	v_fmac_f32_e32 v40, v41, v40
	v_div_scale_f32 v41, vcc, 1.0, v24, 1.0
	v_mul_f32_e32 v46, v41, v40
	v_fma_f32 v47, -v25, v46, v41
	v_fmac_f32_e32 v46, v47, v40
	v_fma_f32 v25, -v25, v46, v41
	v_div_fmas_f32 v25, v25, v40, v46
	v_div_fixup_f32 v24, v25, v24, 1.0
	v_lshlrev_b32_e32 v40, 16, v20
	v_and_b32_e32 v41, 0xffff0000, v20
	v_lshlrev_b32_e32 v20, 16, v21
	v_and_b32_e32 v21, 0xffff0000, v21
	v_mul_f32_e32 v18, v18, v24
	v_mul_f32_e32 v19, v19, v24
	v_mul_f32_e32 v22, v22, v24
	v_mul_f32_e32 v23, v23, v24
	v_mul_f32_e32 v18, v18, v40
	v_mul_f32_e32 v19, v19, v41
	v_mul_f32_e32 v20, v22, v20
	v_mul_f32_e32 v21, v23, v21
	v_cvt_pk_bf16_f32 v18, v18, v19
	v_cvt_pk_bf16_f32 v19, v20, v21
	global_store_dwordx2 v[14:15], v[18:19], off offset:3072
	v_add_f32_dpp v18, v90, v90 quad_perm:[1,0,3,2] row_mask:0xf bank_mask:0xf bound_ctrl:1
	s_nop 1
	v_add_f32_dpp v18, v18, v18 quad_perm:[2,3,0,1] row_mask:0xf bank_mask:0xf bound_ctrl:1
	s_nop 1
	v_add_f32_dpp v18, v18, v18 row_half_mirror row_mask:0xf bank_mask:0xf bound_ctrl:1
	s_nop 1
	v_add_f32_dpp v18, v18, v18 row_mirror row_mask:0xf bank_mask:0xf bound_ctrl:1
	s_nop 0
	v_readlane_b32 s9, v18, 16
	v_readlane_b32 s14, v18, 48
	v_readlane_b32 s6, v18, 0
	v_readlane_b32 s7, v18, 32
	v_mov_b32_e32 v18, s9
	v_mov_b32_e32 v19, s14
	v_add_f32_e32 v18, s6, v18
	v_add_f32_e32 v19, s7, v19
	s_nop 0
	v_add_f32_e32 v18, v18, v19
	v_fmamk_f32 v18, v18, 0x3b800000, v252
	v_cmp_gt_f32_e32 vcc, s55, v18
	v_mul_f32_e32 v19, 0x4f800000, v18
	s_nop 0
	v_cndmask_b32_e32 v18, v18, v19, vcc
	v_sqrt_f32_e32 v19, v18
	s_nop 0
	v_add_u32_e32 v20, -1, v19
	v_fma_f32 v21, -v20, v19, v18
	v_cmp_ge_f32_e64 s[6:7], 0, v21
	v_add_u32_e32 v21, 1, v19
	s_nop 0
	v_cndmask_b32_e64 v20, v19, v20, s[6:7]
	v_fma_f32 v19, -v21, v19, v18
	v_cmp_lt_f32_e64 s[6:7], 0, v19
	s_nop 1
	v_cndmask_b32_e64 v19, v20, v21, s[6:7]
	v_mul_f32_e32 v20, 0x37800000, v19
	v_cndmask_b32_e32 v19, v19, v20, vcc
	v_cmp_class_f32_e32 vcc, v18, v253
	s_nop 1
	v_cndmask_b32_e32 v18, v19, v18, vcc
	v_div_scale_f32 v19, s[6:7], v18, v18, 1.0
	v_rcp_f32_e32 v20, v19
	s_nop 0
	v_fma_f32 v21, -v19, v20, 1.0
	v_fmac_f32_e32 v20, v21, v20
	v_div_scale_f32 v21, vcc, 1.0, v18, 1.0
	v_mul_f32_e32 v22, v21, v20
	v_fma_f32 v23, -v19, v22, v21
	v_fmac_f32_e32 v22, v23, v20
	v_fma_f32 v19, -v19, v22, v21
	v_div_fmas_f32 v19, v19, v20, v22
	v_div_fixup_f32 v18, v19, v18, 1.0
	v_lshlrev_b32_e32 v20, 16, v16
	v_and_b32_e32 v21, 0xffff0000, v16
	v_lshlrev_b32_e32 v16, 16, v17
	v_and_b32_e32 v17, 0xffff0000, v17
	v_mul_f32_e32 v10, v10, v18
	v_mul_f32_e32 v11, v11, v18
	v_mul_f32_e32 v12, v12, v18
	v_mul_f32_e32 v13, v13, v18
	v_mul_f32_e32 v10, v10, v20
	v_mul_f32_e32 v11, v11, v21
	v_mul_f32_e32 v12, v12, v16
	v_mul_f32_e32 v13, v13, v17
	v_cvt_pk_bf16_f32 v10, v10, v11
	v_cvt_pk_bf16_f32 v11, v12, v13
	v_lshl_add_u64 v[12:13], v[6:7], 0, s[40:41]
	global_store_dwordx2 v[14:15], v[10:11], off offset:3584
	v_lshl_add_u64 v[10:11], v[4:5], 0, s[40:41]
	v_lshl_add_u64 v[40:41], v[12:13], 0, v[0:1]
	v_lshl_add_u64 v[12:13], v[8:9], 0, s[40:41]
	v_lshl_add_u64 v[10:11], v[10:11], 0, v[0:1]
	v_lshl_add_u64 v[46:47], v[12:13], 0, v[0:1]
	global_load_dwordx2 v[148:149], v[10:11], off nt
	global_load_dwordx2 v[142:143], v[40:41], off nt
	global_load_dwordx2 v[24:25], v[46:47], off nt
	global_load_dwordx2 v[136:137], v[10:11], off offset:512 nt
	global_load_dwordx2 v[130:131], v[40:41], off offset:512 nt
	global_load_dwordx2 v[22:23], v[46:47], off offset:512 nt
	global_load_dwordx2 v[126:127], v[10:11], off offset:1024 nt
	global_load_dwordx2 v[122:123], v[40:41], off offset:1024 nt
	global_load_dwordx2 v[20:21], v[46:47], off offset:1024 nt
	global_load_dwordx2 v[114:115], v[10:11], off offset:1536 nt
	global_load_dwordx2 v[118:119], v[40:41], off offset:1536 nt
	global_load_dwordx2 v[18:19], v[46:47], off offset:1536 nt
	global_load_dwordx2 v[110:111], v[10:11], off offset:2048 nt
	global_load_dwordx2 v[106:107], v[40:41], off offset:2048 nt
	global_load_dwordx2 v[16:17], v[46:47], off offset:2048 nt
	global_load_dwordx2 v[102:103], v[10:11], off offset:2560 nt
	global_load_dwordx2 v[98:99], v[40:41], off offset:2560 nt
	global_load_dwordx2 v[14:15], v[46:47], off offset:2560 nt
	global_load_dwordx2 v[94:95], v[10:11], off offset:3072 nt
	global_load_dwordx2 v[90:91], v[40:41], off offset:3072 nt
	global_load_dwordx2 v[12:13], v[46:47], off offset:3072 nt
	global_load_dwordx2 v[58:59], v[10:11], off offset:3584 nt
	global_load_dwordx2 v[64:65], v[40:41], off offset:3584 nt
	s_nop 0
	global_load_dwordx2 v[10:11], v[46:47], off offset:3584 nt
	v_lshlrev_b32_e32 v40, 16, v162
	v_and_b32_e32 v41, 0xffff0000, v162
	v_lshlrev_b32_e32 v46, 16, v156
	v_and_b32_e32 v47, 0xffff0000, v156
	v_add_f32_e32 v160, v40, v46
	v_add_f32_e32 v161, v41, v47
	v_lshlrev_b32_e32 v40, 16, v163
	v_and_b32_e32 v41, 0xffff0000, v163
	v_lshlrev_b32_e32 v46, 16, v157
	v_and_b32_e32 v47, 0xffff0000, v157
	v_add_f32_e32 v156, v40, v46
	v_add_f32_e32 v157, v41, v47
	v_mov_b32_e32 v46, v161
	v_mov_b32_e32 v47, v157
	v_mov_b32_e32 v40, v160
	v_mov_b32_e32 v41, v156
	v_mul_f32_e32 v46, v46, v46
	v_mul_f32_e32 v47, v47, v47
	s_nop 0
	v_fma_f32 v40, v40, v40, v46
	v_fma_f32 v41, v41, v41, v47
	v_lshlrev_b32_e32 v46, 16, v144
	v_add_f32_e32 v164, v40, v41
	v_lshlrev_b32_e32 v40, 16, v150
	v_and_b32_e32 v41, 0xffff0000, v150
	v_and_b32_e32 v47, 0xffff0000, v144
	v_add_f32_e32 v154, v40, v46
	v_add_f32_e32 v155, v41, v47
	v_lshlrev_b32_e32 v40, 16, v151
	v_and_b32_e32 v41, 0xffff0000, v151
	v_lshlrev_b32_e32 v46, 16, v145
	v_and_b32_e32 v47, 0xffff0000, v145
	v_add_f32_e32 v150, v40, v46
	v_add_f32_e32 v151, v41, v47
	v_mov_b32_e32 v46, v155
	v_mov_b32_e32 v47, v151
	v_mov_b32_e32 v40, v154
	v_mov_b32_e32 v41, v150
	v_mul_f32_e32 v46, v46, v46
	v_mul_f32_e32 v47, v47, v47
	s_nop 0
	v_fma_f32 v40, v40, v40, v46
	v_fma_f32 v41, v41, v41, v47
	v_lshlrev_b32_e32 v46, 16, v132
	v_add_f32_e32 v166, v40, v41
	v_lshlrev_b32_e32 v40, 16, v138
	v_and_b32_e32 v41, 0xffff0000, v138
	v_and_b32_e32 v47, 0xffff0000, v132
	v_add_f32_e32 v144, v40, v46
	v_add_f32_e32 v145, v41, v47
	v_lshlrev_b32_e32 v40, 16, v139
	v_and_b32_e32 v41, 0xffff0000, v139
	v_lshlrev_b32_e32 v46, 16, v133
	v_and_b32_e32 v47, 0xffff0000, v133
	v_add_f32_e32 v138, v40, v46
	v_add_f32_e32 v139, v41, v47
	v_mov_b32_e32 v46, v145
	v_mov_b32_e32 v47, v139
	v_mov_b32_e32 v40, v144
	v_mov_b32_e32 v41, v138
	v_mul_f32_e32 v46, v46, v46
	v_mul_f32_e32 v47, v47, v47
	s_nop 0
	v_fma_f32 v40, v40, v40, v46
	v_fma_f32 v41, v41, v41, v47
	v_lshlrev_b32_e32 v46, 16, v128
	v_add_f32_e32 v167, v40, v41
	v_lshlrev_b32_e32 v40, 16, v124
	v_and_b32_e32 v41, 0xffff0000, v124
	v_and_b32_e32 v47, 0xffff0000, v128
	v_add_f32_e32 v132, v40, v46
	v_add_f32_e32 v133, v41, v47
	v_lshlrev_b32_e32 v40, 16, v125
	v_and_b32_e32 v41, 0xffff0000, v125
	v_lshlrev_b32_e32 v46, 16, v129
	v_and_b32_e32 v47, 0xffff0000, v129
	v_add_f32_e32 v128, v40, v46
	v_add_f32_e32 v129, v41, v47
	v_mov_b32_e32 v46, v133
	v_mov_b32_e32 v47, v129
	v_mov_b32_e32 v40, v132
	v_mov_b32_e32 v41, v128
	v_mul_f32_e32 v46, v46, v46
	v_mul_f32_e32 v47, v47, v47
	s_nop 0
	v_fma_f32 v40, v40, v40, v46
	v_fma_f32 v41, v41, v41, v47
	v_lshlrev_b32_e32 v46, 16, v116
	v_add_f32_e32 v168, v40, v41
	v_lshlrev_b32_e32 v40, 16, v120
	v_and_b32_e32 v41, 0xffff0000, v120
	v_and_b32_e32 v47, 0xffff0000, v116
	v_add_f32_e32 v124, v40, v46
	v_add_f32_e32 v125, v41, v47
	v_lshlrev_b32_e32 v40, 16, v121
	v_and_b32_e32 v41, 0xffff0000, v121
	v_lshlrev_b32_e32 v46, 16, v117
	v_and_b32_e32 v47, 0xffff0000, v117
	v_add_f32_e32 v120, v40, v46
	v_add_f32_e32 v121, v41, v47
	v_mov_b32_e32 v46, v125
	v_mov_b32_e32 v47, v121
	v_mov_b32_e32 v40, v124
	v_mov_b32_e32 v41, v120
	v_mul_f32_e32 v46, v46, v46
	v_mul_f32_e32 v47, v47, v47
	s_nop 0
	v_fma_f32 v40, v40, v40, v46
	v_fma_f32 v41, v41, v41, v47
	v_lshlrev_b32_e32 v46, 16, v108
	v_add_f32_e32 v163, v40, v41
	v_lshlrev_b32_e32 v40, 16, v112
	v_and_b32_e32 v41, 0xffff0000, v112
	v_and_b32_e32 v47, 0xffff0000, v108
	v_add_f32_e32 v116, v40, v46
	v_add_f32_e32 v117, v41, v47
	v_lshlrev_b32_e32 v40, 16, v113
	v_and_b32_e32 v41, 0xffff0000, v113
	v_lshlrev_b32_e32 v46, 16, v109
	v_and_b32_e32 v47, 0xffff0000, v109
	v_add_f32_e32 v112, v40, v46
	v_add_f32_e32 v113, v41, v47
	v_mov_b32_e32 v46, v117
	v_mov_b32_e32 v47, v113
	v_mov_b32_e32 v40, v116
	v_mov_b32_e32 v41, v112
	v_mul_f32_e32 v46, v46, v46
	v_mul_f32_e32 v47, v47, v47
	s_nop 0
	v_fma_f32 v40, v40, v40, v46
	v_fma_f32 v41, v41, v41, v47
	v_lshlrev_b32_e32 v46, 16, v100
	v_add_f32_e32 v162, v40, v41
	v_lshlrev_b32_e32 v40, 16, v104
	v_and_b32_e32 v41, 0xffff0000, v104
	v_and_b32_e32 v47, 0xffff0000, v100
	v_add_f32_e32 v108, v40, v46
	v_add_f32_e32 v109, v41, v47
	v_lshlrev_b32_e32 v40, 16, v105
	v_and_b32_e32 v41, 0xffff0000, v105
	v_lshlrev_b32_e32 v46, 16, v101
	v_and_b32_e32 v47, 0xffff0000, v101
	v_add_f32_e32 v100, v40, v46
	v_add_f32_e32 v101, v41, v47
	v_mov_b32_e32 v46, v109
	v_mov_b32_e32 v47, v101
	v_mov_b32_e32 v40, v108
	v_mov_b32_e32 v41, v100
	v_mul_f32_e32 v46, v46, v46
	v_mul_f32_e32 v47, v47, v47
	s_nop 0
	v_fma_f32 v40, v40, v40, v46
	v_fma_f32 v41, v41, v41, v47
	v_lshlrev_b32_e32 v46, 16, v96
	v_add_f32_e32 v104, v40, v41
	v_lshlrev_b32_e32 v40, 16, v92
	v_and_b32_e32 v41, 0xffff0000, v92
	v_and_b32_e32 v47, 0xffff0000, v96
	v_add_f32_e32 v40, v40, v46
	v_add_f32_e32 v41, v41, v47
	v_lshlrev_b32_e32 v46, 16, v93
	v_and_b32_e32 v47, 0xffff0000, v93
	v_add_f32_e32 v46, v46, v52
	v_add_f32_e32 v47, v47, v53
	v_mov_b32_e32 v92, v41
	v_mov_b32_e32 v93, v47
	v_mov_b32_e32 v52, v40
	v_mov_b32_e32 v53, v46
	v_mul_f32_e32 v92, v92, v92
	v_mul_f32_e32 v93, v93, v93
	s_nop 0
	v_fma_f32 v52, v52, v52, v92
	v_fma_f32 v53, v53, v53, v93
	v_add_f32_dpp v93, v164, v164 quad_perm:[1,0,3,2] row_mask:0xf bank_mask:0xf bound_ctrl:1
	v_add_f32_e32 v92, v52, v53
	v_lshl_add_u64 v[52:53], v[2:3], 0, s[16:17]
	v_add_f32_dpp v93, v93, v93 quad_perm:[2,3,0,1] row_mask:0xf bank_mask:0xf bound_ctrl:1
	v_lshl_add_u64 v[52:53], v[52:53], 0, v[0:1]
	s_nop 0
	v_add_f32_dpp v93, v93, v93 row_half_mirror row_mask:0xf bank_mask:0xf bound_ctrl:1
	s_nop 1
	v_add_f32_dpp v93, v93, v93 row_mirror row_mask:0xf bank_mask:0xf bound_ctrl:1
	s_nop 0
	v_readlane_b32 s9, v93, 16
	v_readlane_b32 s10, v93, 48
	v_readlane_b32 s6, v93, 0
	v_readlane_b32 s7, v93, 32
	v_mov_b32_e32 v96, s9
	v_mov_b32_e32 v97, s10
	v_add_f32_e32 v96, s6, v96
	v_add_f32_e32 v97, s7, v97
	s_nop 0
	v_add_f32_e32 v93, v96, v97
	v_fmamk_f32 v93, v93, 0x3b800000, v252
	v_cmp_gt_f32_e32 vcc, s55, v93
	v_mul_f32_e32 v96, 0x4f800000, v93
	s_nop 0
	v_cndmask_b32_e32 v93, v93, v96, vcc
	v_sqrt_f32_e32 v96, v93
	s_nop 0
	v_add_u32_e32 v97, -1, v96
	v_fma_f32 v105, -v97, v96, v93
	v_cmp_ge_f32_e64 s[6:7], 0, v105
	v_add_u32_e32 v105, 1, v96
	s_nop 0
	v_cndmask_b32_e64 v97, v96, v97, s[6:7]
	v_fma_f32 v96, -v105, v96, v93
	v_cmp_lt_f32_e64 s[6:7], 0, v96
	s_nop 1
	v_cndmask_b32_e64 v96, v97, v105, s[6:7]
	v_mul_f32_e32 v97, 0x37800000, v96
	v_cndmask_b32_e32 v96, v96, v97, vcc
	v_cmp_class_f32_e32 vcc, v93, v253
	s_nop 1
	v_cndmask_b32_e32 v93, v96, v93, vcc
	v_div_scale_f32 v96, s[6:7], v93, v93, 1.0
	v_rcp_f32_e32 v97, v96
	s_nop 0
	v_fma_f32 v105, -v96, v97, 1.0
	v_fmac_f32_e32 v97, v105, v97
	v_div_scale_f32 v105, vcc, 1.0, v93, 1.0
	v_mul_f32_e32 v164, v105, v97
	v_fma_f32 v165, -v96, v164, v105
	v_fmac_f32_e32 v164, v165, v97
	v_fma_f32 v96, -v96, v164, v105
	v_div_fmas_f32 v96, v96, v97, v164
	v_div_fixup_f32 v96, v96, v93, 1.0
	v_lshlrev_b32_e32 v164, 16, v66
	v_and_b32_e32 v165, 0xffff0000, v66
	v_lshlrev_b32_e32 v66, 16, v67
	v_and_b32_e32 v67, 0xffff0000, v67
	v_mul_f32_e32 v160, v160, v96
	v_mul_f32_e32 v161, v161, v96
	v_mul_f32_e32 v97, v157, v96
	v_mul_f32_e32 v96, v156, v96
	s_nop 0
	v_mul_f32_e32 v66, v96, v66
	v_mul_f32_e32 v67, v97, v67
	v_mul_f32_e32 v96, v160, v164
	v_mul_f32_e32 v97, v161, v165
	s_waitcnt vmcnt(33)
	v_lshlrev_b32_e32 v160, 16, v70
	v_cvt_pk_bf16_f32 v96, v96, v97
	v_cvt_pk_bf16_f32 v97, v66, v67
	v_add_f32_dpp v66, v166, v166 quad_perm:[1,0,3,2] row_mask:0xf bank_mask:0xf bound_ctrl:1
	global_store_dwordx2 v[52:53], v[96:97], off
	v_and_b32_e32 v161, 0xffff0000, v70
	v_add_f32_dpp v66, v66, v66 quad_perm:[2,3,0,1] row_mask:0xf bank_mask:0xf bound_ctrl:1
	v_lshlrev_b32_e32 v70, 16, v71
	v_and_b32_e32 v71, 0xffff0000, v71
	v_add_f32_dpp v66, v66, v66 row_half_mirror row_mask:0xf bank_mask:0xf bound_ctrl:1
	s_nop 1
	v_add_f32_dpp v66, v66, v66 row_mirror row_mask:0xf bank_mask:0xf bound_ctrl:1
	s_nop 0
	v_readlane_b32 s9, v66, 16
	v_readlane_b32 s10, v66, 48
	v_readlane_b32 s6, v66, 0
	v_readlane_b32 s7, v66, 32
	v_mov_b32_e32 v66, s9
	v_mov_b32_e32 v67, s10
	v_add_f32_e32 v66, s6, v66
	v_add_f32_e32 v67, s7, v67
	s_nop 0
	v_add_f32_e32 v66, v66, v67
	v_fmamk_f32 v66, v66, 0x3b800000, v252
	v_cmp_gt_f32_e32 vcc, s55, v66
	v_mul_f32_e32 v67, 0x4f800000, v66
	s_nop 0
	v_cndmask_b32_e32 v66, v66, v67, vcc
	v_sqrt_f32_e32 v67, v66
	s_nop 0
	v_add_u32_e32 v93, -1, v67
	v_fma_f32 v96, -v93, v67, v66
	v_cmp_ge_f32_e64 s[6:7], 0, v96
	v_add_u32_e32 v96, 1, v67
	s_nop 0
	v_cndmask_b32_e64 v93, v67, v93, s[6:7]
	v_fma_f32 v67, -v96, v67, v66
	v_cmp_lt_f32_e64 s[6:7], 0, v67
	s_nop 1
	v_cndmask_b32_e64 v67, v93, v96, s[6:7]
	v_mul_f32_e32 v93, 0x37800000, v67
	v_cndmask_b32_e32 v67, v67, v93, vcc
	v_cmp_class_f32_e32 vcc, v66, v253
	s_nop 1
	v_cndmask_b32_e32 v66, v67, v66, vcc
	v_div_scale_f32 v67, s[6:7], v66, v66, 1.0
	v_rcp_f32_e32 v93, v67
	s_nop 0
	v_fma_f32 v96, -v67, v93, 1.0
	v_fmac_f32_e32 v93, v96, v93
	v_div_scale_f32 v96, vcc, 1.0, v66, 1.0
	v_mul_f32_e32 v97, v96, v93
	v_fma_f32 v105, -v67, v97, v96
	v_fmac_f32_e32 v97, v105, v93
	v_fma_f32 v67, -v67, v97, v96
	v_div_fmas_f32 v67, v67, v93, v97
	v_div_fixup_f32 v66, v67, v66, 1.0
	v_lshlrev_b32_e32 v96, 16, v60
	v_and_b32_e32 v97, 0xffff0000, v60
	v_lshlrev_b32_e32 v60, 16, v61
	v_and_b32_e32 v61, 0xffff0000, v61
	v_mul_f32_e32 v154, v154, v66
	v_mul_f32_e32 v155, v155, v66
	v_mul_f32_e32 v67, v151, v66
	v_mul_f32_e32 v66, v150, v66
	s_nop 0
	v_mul_f32_e32 v60, v66, v60
	v_mul_f32_e32 v61, v67, v61
	v_mul_f32_e32 v66, v154, v96
	v_mul_f32_e32 v67, v155, v97
	v_lshlrev_b32_e32 v154, 16, v152
	v_cvt_pk_bf16_f32 v66, v66, v67
	v_cvt_pk_bf16_f32 v67, v60, v61
	v_add_f32_dpp v60, v167, v167 quad_perm:[1,0,3,2] row_mask:0xf bank_mask:0xf bound_ctrl:1
	global_store_dwordx2 v[52:53], v[66:67], off offset:512
	v_and_b32_e32 v155, 0xffff0000, v152
	v_add_f32_dpp v60, v60, v60 quad_perm:[2,3,0,1] row_mask:0xf bank_mask:0xf bound_ctrl:1
	v_lshlrev_b32_e32 v152, 16, v153
	v_and_b32_e32 v153, 0xffff0000, v153
	v_add_f32_dpp v60, v60, v60 row_half_mirror row_mask:0xf bank_mask:0xf bound_ctrl:1
	s_nop 1
	v_add_f32_dpp v60, v60, v60 row_mirror row_mask:0xf bank_mask:0xf bound_ctrl:1
	s_nop 0
	v_readlane_b32 s9, v60, 16
	v_readlane_b32 s10, v60, 48
	v_readlane_b32 s6, v60, 0
	v_readlane_b32 s7, v60, 32
	v_mov_b32_e32 v60, s9
	v_mov_b32_e32 v61, s10
	v_add_f32_e32 v60, s6, v60
	v_add_f32_e32 v61, s7, v61
	s_nop 0
	v_add_f32_e32 v60, v60, v61
	v_fmamk_f32 v60, v60, 0x3b800000, v252
	v_cmp_gt_f32_e32 vcc, s55, v60
	v_mul_f32_e32 v61, 0x4f800000, v60
	s_nop 0
	v_cndmask_b32_e32 v60, v60, v61, vcc
	v_sqrt_f32_e32 v61, v60
	s_nop 0
	v_add_u32_e32 v66, -1, v61
	v_fma_f32 v67, -v66, v61, v60
	v_cmp_ge_f32_e64 s[6:7], 0, v67
	v_add_u32_e32 v67, 1, v61
	s_nop 0
	v_cndmask_b32_e64 v66, v61, v66, s[6:7]
	v_fma_f32 v61, -v67, v61, v60
	v_cmp_lt_f32_e64 s[6:7], 0, v61
	s_nop 1
	v_cndmask_b32_e64 v61, v66, v67, s[6:7]
	v_mul_f32_e32 v66, 0x37800000, v61
	v_cndmask_b32_e32 v61, v61, v66, vcc
	v_cmp_class_f32_e32 vcc, v60, v253
	s_nop 1
	v_cndmask_b32_e32 v60, v61, v60, vcc
	v_div_scale_f32 v61, s[6:7], v60, v60, 1.0
	v_rcp_f32_e32 v66, v61
	s_nop 0
	v_fma_f32 v67, -v61, v66, 1.0
	v_fmac_f32_e32 v66, v67, v66
	v_div_scale_f32 v67, vcc, 1.0, v60, 1.0
	v_mul_f32_e32 v93, v67, v66
	v_fma_f32 v96, -v61, v93, v67
	v_fmac_f32_e32 v93, v96, v66
	v_fma_f32 v61, -v61, v93, v67
	v_div_fmas_f32 v61, v61, v66, v93
	v_div_fixup_f32 v60, v61, v60, 1.0
	v_lshlrev_b32_e32 v66, 16, v54
	v_and_b32_e32 v67, 0xffff0000, v54
	v_lshlrev_b32_e32 v54, 16, v55
	v_and_b32_e32 v55, 0xffff0000, v55
	v_mul_f32_e32 v96, v144, v60
	v_mul_f32_e32 v97, v145, v60
	v_mul_f32_e32 v61, v139, v60
	v_mul_f32_e32 v60, v138, v60
	s_nop 0
	v_mul_f32_e32 v54, v60, v54
	v_mul_f32_e32 v55, v61, v55
	v_mul_f32_e32 v60, v96, v66
	v_mul_f32_e32 v61, v97, v67
	s_nop 0
	v_cvt_pk_bf16_f32 v60, v60, v61
	v_cvt_pk_bf16_f32 v61, v54, v55
	v_add_f32_dpp v54, v168, v168 quad_perm:[1,0,3,2] row_mask:0xf bank_mask:0xf bound_ctrl:1
	global_store_dwordx2 v[52:53], v[60:61], off offset:1024
	s_nop 0
	v_add_f32_dpp v54, v54, v54 quad_perm:[2,3,0,1] row_mask:0xf bank_mask:0xf bound_ctrl:1
	s_nop 1
	v_add_f32_dpp v54, v54, v54 row_half_mirror row_mask:0xf bank_mask:0xf bound_ctrl:1
	s_nop 1
	v_add_f32_dpp v54, v54, v54 row_mirror row_mask:0xf bank_mask:0xf bound_ctrl:1
	s_nop 0
	v_readlane_b32 s9, v54, 16
	v_readlane_b32 s10, v54, 48
	v_readlane_b32 s6, v54, 0
	v_readlane_b32 s7, v54, 32
	v_mov_b32_e32 v54, s9
	v_mov_b32_e32 v55, s10
	v_add_f32_e32 v54, s6, v54
	v_add_f32_e32 v55, s7, v55
	s_nop 0
	v_add_f32_e32 v54, v54, v55
	v_fmamk_f32 v54, v54, 0x3b800000, v252
	v_cmp_gt_f32_e32 vcc, s55, v54
	v_mul_f32_e32 v55, 0x4f800000, v54
	s_nop 0
	v_cndmask_b32_e32 v54, v54, v55, vcc
	v_sqrt_f32_e32 v55, v54
	s_nop 0
	v_add_u32_e32 v60, -1, v55
	v_fma_f32 v61, -v60, v55, v54
	v_cmp_ge_f32_e64 s[6:7], 0, v61
	v_add_u32_e32 v61, 1, v55
	s_nop 0
	v_cndmask_b32_e64 v60, v55, v60, s[6:7]
	v_fma_f32 v55, -v61, v55, v54
	v_cmp_lt_f32_e64 s[6:7], 0, v55
	s_nop 1
	v_cndmask_b32_e64 v55, v60, v61, s[6:7]
	v_mul_f32_e32 v60, 0x37800000, v55
	v_cndmask_b32_e32 v55, v55, v60, vcc
	v_cmp_class_f32_e32 vcc, v54, v253
	s_nop 1
	v_cndmask_b32_e32 v54, v55, v54, vcc
	v_div_scale_f32 v55, s[6:7], v54, v54, 1.0
	v_rcp_f32_e32 v60, v55
	s_nop 0
	v_fma_f32 v61, -v55, v60, 1.0
	v_fmac_f32_e32 v60, v61, v60
	v_div_scale_f32 v61, vcc, 1.0, v54, 1.0
	v_mul_f32_e32 v66, v61, v60
	v_fma_f32 v67, -v55, v66, v61
	v_fmac_f32_e32 v66, v67, v60
	v_fma_f32 v55, -v55, v66, v61
	v_div_fmas_f32 v55, v55, v60, v66
	v_div_fixup_f32 v54, v55, v54, 1.0
	v_lshlrev_b32_e32 v60, 16, v48
	v_and_b32_e32 v61, 0xffff0000, v48
	v_lshlrev_b32_e32 v48, 16, v49
	v_and_b32_e32 v49, 0xffff0000, v49
	v_mul_f32_e32 v66, v132, v54
	v_mul_f32_e32 v67, v133, v54
	v_mul_f32_e32 v55, v129, v54
	v_mul_f32_e32 v54, v128, v54
	s_nop 0
	v_mul_f32_e32 v48, v54, v48
	v_mul_f32_e32 v49, v55, v49
	v_mul_f32_e32 v54, v66, v60
	v_mul_f32_e32 v55, v67, v61
	s_nop 0
	v_cvt_pk_bf16_f32 v54, v54, v55
	v_cvt_pk_bf16_f32 v55, v48, v49
	v_add_f32_dpp v48, v163, v163 quad_perm:[1,0,3,2] row_mask:0xf bank_mask:0xf bound_ctrl:1
	global_store_dwordx2 v[52:53], v[54:55], off offset:1536
	s_nop 0
	v_add_f32_dpp v48, v48, v48 quad_perm:[2,3,0,1] row_mask:0xf bank_mask:0xf bound_ctrl:1
	s_nop 1
	v_add_f32_dpp v48, v48, v48 row_half_mirror row_mask:0xf bank_mask:0xf bound_ctrl:1
	s_nop 1
	v_add_f32_dpp v48, v48, v48 row_mirror row_mask:0xf bank_mask:0xf bound_ctrl:1
	s_nop 0
	v_readlane_b32 s9, v48, 16
	v_readlane_b32 s10, v48, 48
	v_readlane_b32 s6, v48, 0
	v_readlane_b32 s7, v48, 32
	v_mov_b32_e32 v48, s9
	v_mov_b32_e32 v49, s10
	v_add_f32_e32 v48, s6, v48
	v_add_f32_e32 v49, s7, v49
	s_nop 0
	v_add_f32_e32 v48, v48, v49
	v_fmamk_f32 v48, v48, 0x3b800000, v252
	v_cmp_gt_f32_e32 vcc, s55, v48
	v_mul_f32_e32 v49, 0x4f800000, v48
	s_nop 0
	v_cndmask_b32_e32 v48, v48, v49, vcc
	v_sqrt_f32_e32 v49, v48
	s_nop 0
	v_add_u32_e32 v54, -1, v49
	v_fma_f32 v55, -v54, v49, v48
	v_cmp_ge_f32_e64 s[6:7], 0, v55
	v_add_u32_e32 v55, 1, v49
	s_nop 0
	v_cndmask_b32_e64 v54, v49, v54, s[6:7]
	v_fma_f32 v49, -v55, v49, v48
	v_cmp_lt_f32_e64 s[6:7], 0, v49
	s_nop 1
	v_cndmask_b32_e64 v49, v54, v55, s[6:7]
	v_mul_f32_e32 v54, 0x37800000, v49
	v_cndmask_b32_e32 v49, v49, v54, vcc
	v_cmp_class_f32_e32 vcc, v48, v253
	s_nop 1
	v_cndmask_b32_e32 v48, v49, v48, vcc
	v_div_scale_f32 v49, s[6:7], v48, v48, 1.0
	v_rcp_f32_e32 v54, v49
	s_nop 0
	v_fma_f32 v55, -v49, v54, 1.0
	v_fmac_f32_e32 v54, v55, v54
	v_div_scale_f32 v55, vcc, 1.0, v48, 1.0
	v_mul_f32_e32 v60, v55, v54
	v_fma_f32 v61, -v49, v60, v55
	v_fmac_f32_e32 v60, v61, v54
	v_fma_f32 v49, -v49, v60, v55
	v_div_fmas_f32 v49, v49, v54, v60
	v_div_fixup_f32 v48, v49, v48, 1.0
	v_lshlrev_b32_e32 v54, 16, v42
	v_and_b32_e32 v55, 0xffff0000, v42
	v_lshlrev_b32_e32 v42, 16, v43
	v_and_b32_e32 v43, 0xffff0000, v43
	v_mul_f32_e32 v60, v124, v48
	v_mul_f32_e32 v61, v125, v48
	v_mul_f32_e32 v49, v121, v48
	v_mul_f32_e32 v48, v120, v48
	s_nop 0
	v_mul_f32_e32 v42, v48, v42
	v_mul_f32_e32 v43, v49, v43
	v_mul_f32_e32 v48, v60, v54
	v_mul_f32_e32 v49, v61, v55
	s_nop 0
	v_cvt_pk_bf16_f32 v48, v48, v49
	v_cvt_pk_bf16_f32 v49, v42, v43
	v_add_f32_dpp v42, v162, v162 quad_perm:[1,0,3,2] row_mask:0xf bank_mask:0xf bound_ctrl:1
	global_store_dwordx2 v[52:53], v[48:49], off offset:2048
	s_nop 0
	v_add_f32_dpp v42, v42, v42 quad_perm:[2,3,0,1] row_mask:0xf bank_mask:0xf bound_ctrl:1
; template <bool HG>
; __device__ __forceinline__ void readout_phase2(const Args& a, Frame& F, const float* gain, int nrows) {
;     ...
;     const bool cx = ML + nw < nrows;
	s_nop 1
	v_add_f32_dpp v42, v42, v42 row_half_mirror row_mask:0xf bank_mask:0xf bound_ctrl:1
	s_nop 1
	v_add_f32_dpp v42, v42, v42 row_mirror row_mask:0xf bank_mask:0xf bound_ctrl:1
	s_nop 0
	v_readlane_b32 s9, v42, 16
	v_readlane_b32 s10, v42, 48
	v_readlane_b32 s6, v42, 0
	v_readlane_b32 s7, v42, 32
	v_mov_b32_e32 v42, s9
	v_mov_b32_e32 v43, s10
	v_add_f32_e32 v42, s6, v42
	v_add_f32_e32 v43, s7, v43
	s_nop 0
	v_add_f32_e32 v42, v42, v43
	v_fmamk_f32 v42, v42, 0x3b800000, v252
	v_cmp_gt_f32_e32 vcc, s55, v42
	v_mul_f32_e32 v43, 0x4f800000, v42
	s_nop 0
	v_cndmask_b32_e32 v42, v42, v43, vcc
	v_sqrt_f32_e32 v43, v42
	s_nop 0
	v_add_u32_e32 v48, -1, v43
	v_fma_f32 v49, -v48, v43, v42
	v_cmp_ge_f32_e64 s[6:7], 0, v49
	v_add_u32_e32 v49, 1, v43
	s_nop 0
	v_cndmask_b32_e64 v48, v43, v48, s[6:7]
	v_fma_f32 v43, -v49, v43, v42
	v_cmp_lt_f32_e64 s[6:7], 0, v43
	s_nop 1
	v_cndmask_b32_e64 v43, v48, v49, s[6:7]
	v_mul_f32_e32 v48, 0x37800000, v43
	v_cndmask_b32_e32 v43, v43, v48, vcc
	v_cmp_class_f32_e32 vcc, v42, v253
	s_nop 1
	v_cndmask_b32_e32 v42, v43, v42, vcc
	v_div_scale_f32 v43, s[6:7], v42, v42, 1.0
	v_rcp_f32_e32 v48, v43
	s_nop 0
	v_fma_f32 v49, -v43, v48, 1.0
	v_fmac_f32_e32 v48, v49, v48
	v_div_scale_f32 v49, vcc, 1.0, v42, 1.0
	v_mul_f32_e32 v54, v49, v48
	v_fma_f32 v55, -v43, v54, v49
	v_fmac_f32_e32 v54, v55, v48
	v_fma_f32 v43, -v43, v54, v49
	v_div_fmas_f32 v43, v43, v48, v54
	v_div_fixup_f32 v42, v43, v42, 1.0
	v_lshlrev_b32_e32 v48, 16, v36
	v_and_b32_e32 v49, 0xffff0000, v36
	v_lshlrev_b32_e32 v36, 16, v37
	v_and_b32_e32 v37, 0xffff0000, v37
	v_mul_f32_e32 v54, v116, v42
	v_mul_f32_e32 v55, v117, v42
	v_mul_f32_e32 v43, v113, v42
	v_mul_f32_e32 v42, v112, v42
	s_nop 0
	v_mul_f32_e32 v36, v42, v36
	v_mul_f32_e32 v37, v43, v37
	v_mul_f32_e32 v42, v54, v48
	v_mul_f32_e32 v43, v55, v49
	s_nop 0
	v_cvt_pk_bf16_f32 v42, v42, v43
	v_cvt_pk_bf16_f32 v43, v36, v37
	v_add_f32_dpp v36, v104, v104 quad_perm:[1,0,3,2] row_mask:0xf bank_mask:0xf bound_ctrl:1
	global_store_dwordx2 v[52:53], v[42:43], off offset:2560
	s_nop 0
	v_add_f32_dpp v36, v36, v36 quad_perm:[2,3,0,1] row_mask:0xf bank_mask:0xf bound_ctrl:1
	s_nop 1
	v_add_f32_dpp v36, v36, v36 row_half_mirror row_mask:0xf bank_mask:0xf bound_ctrl:1
	s_nop 1
	v_add_f32_dpp v36, v36, v36 row_mirror row_mask:0xf bank_mask:0xf bound_ctrl:1
	s_nop 0
	v_readlane_b32 s9, v36, 16
	v_readlane_b32 s10, v36, 48
	v_readlane_b32 s6, v36, 0
	v_readlane_b32 s7, v36, 32
	v_mov_b32_e32 v36, s9
	v_mov_b32_e32 v37, s10
	v_add_f32_e32 v36, s6, v36
	v_add_f32_e32 v37, s7, v37
	s_nop 0
	v_add_f32_e32 v36, v36, v37
	v_fmamk_f32 v36, v36, 0x3b800000, v252
	v_cmp_gt_f32_e32 vcc, s55, v36
	v_mul_f32_e32 v37, 0x4f800000, v36
	s_nop 0
	v_cndmask_b32_e32 v36, v36, v37, vcc
	v_sqrt_f32_e32 v37, v36
	s_nop 0
	v_add_u32_e32 v42, -1, v37
	v_fma_f32 v43, -v42, v37, v36
	v_cmp_ge_f32_e64 s[6:7], 0, v43
	v_add_u32_e32 v43, 1, v37
	s_nop 0
	v_cndmask_b32_e64 v42, v37, v42, s[6:7]
	v_fma_f32 v37, -v43, v37, v36
	v_cmp_lt_f32_e64 s[6:7], 0, v37
	s_nop 1
	v_cndmask_b32_e64 v37, v42, v43, s[6:7]
	v_mul_f32_e32 v42, 0x37800000, v37
	v_cndmask_b32_e32 v37, v37, v42, vcc
	v_cmp_class_f32_e32 vcc, v36, v253
	s_nop 1
	v_cndmask_b32_e32 v36, v37, v36, vcc
	v_div_scale_f32 v37, s[6:7], v36, v36, 1.0
	v_rcp_f32_e32 v42, v37
	s_nop 0
	v_fma_f32 v43, -v37, v42, 1.0
	v_fmac_f32_e32 v42, v43, v42
	v_div_scale_f32 v43, vcc, 1.0, v36, 1.0
	v_mul_f32_e32 v48, v43, v42
	v_fma_f32 v49, -v37, v48, v43
	v_fmac_f32_e32 v48, v49, v42
	v_fma_f32 v37, -v37, v48, v43
	v_div_fmas_f32 v37, v37, v42, v48
	v_div_fixup_f32 v36, v37, v36, 1.0
	v_lshlrev_b32_e32 v42, 16, v32
	v_and_b32_e32 v43, 0xffff0000, v32
	v_lshlrev_b32_e32 v32, 16, v33
	v_and_b32_e32 v33, 0xffff0000, v33
	v_mul_f32_e32 v48, v108, v36
	v_mul_f32_e32 v49, v109, v36
	v_mul_f32_e32 v37, v101, v36
	v_mul_f32_e32 v36, v100, v36
	s_nop 0
	v_mul_f32_e32 v32, v36, v32
	v_mul_f32_e32 v33, v37, v33
	v_mul_f32_e32 v36, v48, v42
	v_mul_f32_e32 v37, v49, v43
	s_nop 0
	v_cvt_pk_bf16_f32 v36, v36, v37
	v_cvt_pk_bf16_f32 v37, v32, v33
	v_add_f32_dpp v32, v92, v92 quad_perm:[1,0,3,2] row_mask:0xf bank_mask:0xf bound_ctrl:1
	global_store_dwordx2 v[52:53], v[36:37], off offset:3072
	s_nop 0
	v_add_f32_dpp v32, v32, v32 quad_perm:[2,3,0,1] row_mask:0xf bank_mask:0xf bound_ctrl:1
	s_nop 1
	v_add_f32_dpp v32, v32, v32 row_half_mirror row_mask:0xf bank_mask:0xf bound_ctrl:1
	s_nop 1
	v_add_f32_dpp v32, v32, v32 row_mirror row_mask:0xf bank_mask:0xf bound_ctrl:1
	s_nop 0
	v_readlane_b32 s9, v32, 16
	v_readlane_b32 s10, v32, 48
	v_readlane_b32 s6, v32, 0
	v_readlane_b32 s7, v32, 32
	v_mov_b32_e32 v32, s9
	v_mov_b32_e32 v33, s10
	v_add_f32_e32 v32, s6, v32
	v_add_f32_e32 v33, s7, v33
	s_add_i32 s10, s8, 0x3800
	v_add_f32_e32 v32, v32, v33
	v_fmamk_f32 v32, v32, 0x3b800000, v252
	v_cmp_gt_f32_e32 vcc, s55, v32
	v_mul_f32_e32 v33, 0x4f800000, v32
	s_ashr_i32 s11, s10, 31
	v_cndmask_b32_e32 v32, v32, v33, vcc
	v_sqrt_f32_e32 v33, v32
	s_lshl_b64 s[78:79], s[10:11], 12
	s_cmp_lt_i32 s82, s47
	v_add_u32_e32 v36, -1, v33
	v_fma_f32 v37, -v36, v33, v32
	v_cmp_ge_f32_e64 s[6:7], 0, v37
	v_add_u32_e32 v37, 1, v33
	s_nop 0
	v_cndmask_b32_e64 v36, v33, v36, s[6:7]
	v_fma_f32 v33, -v37, v33, v32
	v_cmp_lt_f32_e64 s[6:7], 0, v33
	s_nop 1
	v_cndmask_b32_e64 v33, v36, v37, s[6:7]
	v_mul_f32_e32 v36, 0x37800000, v33
	v_cndmask_b32_e32 v33, v33, v36, vcc
	v_cmp_class_f32_e32 vcc, v32, v253
	s_nop 1
	v_cndmask_b32_e32 v32, v33, v32, vcc
	v_div_scale_f32 v33, s[6:7], v32, v32, 1.0
	v_rcp_f32_e32 v36, v33
	s_nop 0
	v_fma_f32 v37, -v33, v36, 1.0
	v_fmac_f32_e32 v36, v37, v36
	v_div_scale_f32 v37, vcc, 1.0, v32, 1.0
	v_mul_f32_e32 v42, v37, v36
	v_fma_f32 v43, -v33, v42, v37
	v_fmac_f32_e32 v42, v43, v36
	v_fma_f32 v33, -v33, v42, v37
	v_div_fmas_f32 v33, v33, v36, v42
	v_div_fixup_f32 v32, v33, v32, 1.0
	v_lshlrev_b32_e32 v36, 16, v28
	v_and_b32_e32 v37, 0xffff0000, v28
	v_lshlrev_b32_e32 v28, 16, v29
	v_and_b32_e32 v29, 0xffff0000, v29
	v_mul_f32_e32 v40, v40, v32
	v_mul_f32_e32 v41, v41, v32
	v_mul_f32_e32 v33, v47, v32
	v_mul_f32_e32 v32, v46, v32
	s_nop 0
	v_mul_f32_e32 v28, v32, v28
	v_mul_f32_e32 v29, v33, v29
	v_mul_f32_e32 v32, v40, v36
	v_mul_f32_e32 v33, v41, v37
	s_nop 0
	v_cvt_pk_bf16_f32 v32, v32, v33
	v_cvt_pk_bf16_f32 v33, v28, v29
	global_store_dwordx2 v[52:53], v[32:33], off offset:3584
	v_lshl_add_u64 v[32:33], v[6:7], 0, s[78:79]
	v_lshl_add_u64 v[28:29], v[4:5], 0, s[78:79]
	v_lshl_add_u64 v[60:61], v[32:33], 0, v[0:1]
	v_lshl_add_u64 v[32:33], v[8:9], 0, s[78:79]
	v_lshl_add_u64 v[28:29], v[28:29], 0, v[0:1]
	v_lshl_add_u64 v[150:151], v[32:33], 0, v[0:1]
	global_load_dwordx2 v[144:145], v[28:29], off nt
	global_load_dwordx2 v[138:139], v[60:61], off nt
	global_load_dwordx2 v[52:53], v[150:151], off nt
	global_load_dwordx2 v[132:133], v[28:29], off offset:512 nt
	global_load_dwordx2 v[128:129], v[60:61], off offset:512 nt
	global_load_dwordx2 v[48:49], v[150:151], off offset:512 nt
	global_load_dwordx2 v[124:125], v[28:29], off offset:1024 nt
	global_load_dwordx2 v[120:121], v[60:61], off offset:1024 nt
	global_load_dwordx2 v[46:47], v[150:151], off offset:1024 nt
	global_load_dwordx2 v[112:113], v[28:29], off offset:1536 nt
	global_load_dwordx2 v[116:117], v[60:61], off offset:1536 nt
	global_load_dwordx2 v[42:43], v[150:151], off offset:1536 nt
	global_load_dwordx2 v[108:109], v[28:29], off offset:2048 nt
	global_load_dwordx2 v[104:105], v[60:61], off offset:2048 nt
	global_load_dwordx2 v[40:41], v[150:151], off offset:2048 nt
	global_load_dwordx2 v[100:101], v[28:29], off offset:2560 nt
	global_load_dwordx2 v[96:97], v[60:61], off offset:2560 nt
	global_load_dwordx2 v[36:37], v[150:151], off offset:2560 nt
	global_load_dwordx2 v[92:93], v[28:29], off offset:3072 nt
	global_load_dwordx2 v[66:67], v[60:61], off offset:3072 nt
	global_load_dwordx2 v[32:33], v[150:151], off offset:3072 nt
	global_load_dwordx2 v[54:55], v[28:29], off offset:3584 nt
	s_nop 0
	global_load_dwordx2 v[60:61], v[60:61], off offset:3584 nt
	s_nop 0
	global_load_dwordx2 v[28:29], v[150:151], off offset:3584 nt
	v_lshlrev_b32_e32 v150, 16, v158
	v_and_b32_e32 v151, 0xffff0000, v158
	v_add_f32_e32 v154, v150, v154
	v_add_f32_e32 v155, v151, v155
	v_lshlrev_b32_e32 v150, 16, v159
	v_and_b32_e32 v151, 0xffff0000, v159
	v_add_f32_e32 v152, v150, v152
	v_add_f32_e32 v153, v151, v153
	v_mov_b32_e32 v156, v155
	v_mov_b32_e32 v157, v153
	v_mov_b32_e32 v150, v154
	v_mov_b32_e32 v151, v152
	v_mul_f32_e32 v156, v156, v156
	v_mul_f32_e32 v157, v157, v157
	s_nop 0
	v_fma_f32 v150, v150, v150, v156
	v_fma_f32 v151, v151, v151, v157
	v_lshlrev_b32_e32 v156, 16, v140
	v_add_f32_e32 v162, v150, v151
	v_lshlrev_b32_e32 v150, 16, v146
	v_and_b32_e32 v151, 0xffff0000, v146
	v_and_b32_e32 v157, 0xffff0000, v140
	v_lshlrev_b32_e32 v146, 16, v147
	v_and_b32_e32 v147, 0xffff0000, v147
	v_lshlrev_b32_e32 v140, 16, v141
	v_and_b32_e32 v141, 0xffff0000, v141
	v_add_f32_e32 v150, v150, v156
	v_add_f32_e32 v151, v151, v157
	v_add_f32_e32 v146, v146, v140
	v_add_f32_e32 v147, v147, v141
	v_mov_b32_e32 v156, v151
	v_mov_b32_e32 v157, v147
	v_mov_b32_e32 v140, v150
	v_mov_b32_e32 v141, v146
	v_mul_f32_e32 v156, v156, v156
	v_mul_f32_e32 v157, v157, v157
	s_nop 0
	v_fma_f32 v140, v140, v140, v156
	v_fma_f32 v141, v141, v141, v157
	v_lshlrev_b32_e32 v156, 16, v88
	v_add_f32_e32 v164, v140, v141
	v_lshlrev_b32_e32 v140, 16, v134
	v_and_b32_e32 v141, 0xffff0000, v134
	v_and_b32_e32 v157, 0xffff0000, v88
	v_lshlrev_b32_e32 v134, 16, v135
	v_and_b32_e32 v135, 0xffff0000, v135
	v_lshlrev_b32_e32 v88, 16, v89
	v_and_b32_e32 v89, 0xffff0000, v89
	v_add_f32_e32 v140, v140, v156
	v_add_f32_e32 v141, v141, v157
	v_add_f32_e32 v134, v134, v88
	v_add_f32_e32 v135, v135, v89
	v_mov_b32_e32 v156, v141
	v_mov_b32_e32 v157, v135
	v_mov_b32_e32 v88, v140
	v_mov_b32_e32 v89, v134
	v_mul_f32_e32 v156, v156, v156
	v_mul_f32_e32 v157, v157, v157
	s_nop 0
	v_fma_f32 v88, v88, v88, v156
	v_fma_f32 v89, v89, v89, v157
	v_lshlrev_b32_e32 v156, 16, v86
	v_add_f32_e32 v165, v88, v89
	v_lshlrev_b32_e32 v88, 16, v84
	v_and_b32_e32 v89, 0xffff0000, v84
	v_and_b32_e32 v157, 0xffff0000, v86
	v_lshlrev_b32_e32 v84, 16, v85
	v_and_b32_e32 v85, 0xffff0000, v85
	v_lshlrev_b32_e32 v86, 16, v87
	v_and_b32_e32 v87, 0xffff0000, v87
	v_add_f32_e32 v88, v88, v156
	v_add_f32_e32 v89, v89, v157
	v_add_f32_e32 v86, v84, v86
	v_add_f32_e32 v87, v85, v87
	v_mov_b32_e32 v156, v89
	v_mov_b32_e32 v157, v87
	v_mov_b32_e32 v84, v88
	v_mov_b32_e32 v85, v86
	v_mul_f32_e32 v156, v156, v156
	v_mul_f32_e32 v157, v157, v157
	s_nop 0
	v_fma_f32 v84, v84, v84, v156
	v_fma_f32 v85, v85, v85, v157
	v_lshlrev_b32_e32 v156, 16, v80
	v_add_f32_e32 v166, v84, v85
	v_lshlrev_b32_e32 v84, 16, v82
	v_and_b32_e32 v85, 0xffff0000, v82
	v_and_b32_e32 v157, 0xffff0000, v80
	v_lshlrev_b32_e32 v82, 16, v83
	v_and_b32_e32 v83, 0xffff0000, v83
	v_lshlrev_b32_e32 v80, 16, v81
	v_and_b32_e32 v81, 0xffff0000, v81
	v_add_f32_e32 v84, v84, v156
	v_add_f32_e32 v85, v85, v157
	v_add_f32_e32 v82, v82, v80
	v_add_f32_e32 v83, v83, v81
	v_mov_b32_e32 v156, v85
	v_mov_b32_e32 v157, v83
	v_mov_b32_e32 v80, v84
	v_mov_b32_e32 v81, v82
	v_mul_f32_e32 v156, v156, v156
	v_mul_f32_e32 v157, v157, v157
	s_nop 0
	v_fma_f32 v80, v80, v80, v156
	v_fma_f32 v81, v81, v81, v157
	v_lshlrev_b32_e32 v156, 16, v76
	v_add_f32_e32 v159, v80, v81
	v_lshlrev_b32_e32 v80, 16, v78
	v_and_b32_e32 v81, 0xffff0000, v78
	v_and_b32_e32 v157, 0xffff0000, v76
	v_lshlrev_b32_e32 v78, 16, v79
	v_and_b32_e32 v79, 0xffff0000, v79
	v_lshlrev_b32_e32 v76, 16, v77
	v_and_b32_e32 v77, 0xffff0000, v77
	v_add_f32_e32 v80, v80, v156
	v_add_f32_e32 v81, v81, v157
	v_add_f32_e32 v78, v78, v76
	v_add_f32_e32 v79, v79, v77
	v_mov_b32_e32 v156, v81
	v_mov_b32_e32 v157, v79
	v_mov_b32_e32 v76, v80
	v_mov_b32_e32 v77, v78
	v_mul_f32_e32 v156, v156, v156
	v_mul_f32_e32 v157, v157, v157
	s_nop 0
	v_fma_f32 v76, v76, v76, v156
	v_fma_f32 v77, v77, v77, v157
	v_lshlrev_b32_e32 v156, 16, v72
	v_add_f32_e32 v158, v76, v77
	v_lshlrev_b32_e32 v76, 16, v74
	v_and_b32_e32 v77, 0xffff0000, v74
	v_and_b32_e32 v157, 0xffff0000, v72
	v_lshlrev_b32_e32 v74, 16, v75
	v_and_b32_e32 v75, 0xffff0000, v75
	v_lshlrev_b32_e32 v72, 16, v73
	v_and_b32_e32 v73, 0xffff0000, v73
	v_add_f32_e32 v76, v76, v156
	v_add_f32_e32 v77, v77, v157
	v_add_f32_e32 v74, v74, v72
	v_add_f32_e32 v75, v75, v73
	v_mov_b32_e32 v156, v77
	v_mov_b32_e32 v157, v75
	v_mov_b32_e32 v72, v76
	v_mov_b32_e32 v73, v74
	v_mul_f32_e32 v156, v156, v156
	v_mul_f32_e32 v157, v157, v157
	s_nop 0
	v_fma_f32 v72, v72, v72, v156
	v_fma_f32 v73, v73, v73, v157
	s_nop 0
	v_add_f32_e32 v157, v72, v73
	v_lshlrev_b32_e32 v72, 16, v68
	v_and_b32_e32 v73, 0xffff0000, v68
	v_lshlrev_b32_e32 v68, 16, v69
	v_and_b32_e32 v69, 0xffff0000, v69
	v_add_f32_e32 v72, v72, v160
	v_add_f32_e32 v73, v73, v161
	v_add_f32_e32 v68, v68, v70
	v_add_f32_e32 v69, v69, v71
	v_mov_b32_e32 v160, v73
	v_mov_b32_e32 v161, v69
	v_mov_b32_e32 v70, v72
	v_mov_b32_e32 v71, v68
	v_mul_f32_e32 v160, v160, v160
	v_mul_f32_e32 v161, v161, v161
	s_nop 0
	v_fma_f32 v70, v70, v70, v160
	v_fma_f32 v71, v71, v71, v161
	v_add_f32_dpp v160, v162, v162 quad_perm:[1,0,3,2] row_mask:0xf bank_mask:0xf bound_ctrl:1
	v_add_f32_e32 v156, v70, v71
	v_lshl_add_u64 v[70:71], v[2:3], 0, s[12:13]
	v_add_f32_dpp v160, v160, v160 quad_perm:[2,3,0,1] row_mask:0xf bank_mask:0xf bound_ctrl:1
	v_lshl_add_u64 v[70:71], v[70:71], 0, v[0:1]
	s_nop 0
	v_add_f32_dpp v160, v160, v160 row_half_mirror row_mask:0xf bank_mask:0xf bound_ctrl:1
	s_nop 1
	v_add_f32_dpp v160, v160, v160 row_mirror row_mask:0xf bank_mask:0xf bound_ctrl:1
	s_nop 0
	v_readlane_b32 s9, v160, 16
	v_readlane_b32 s11, v160, 48
	v_readlane_b32 s6, v160, 0
	v_readlane_b32 s7, v160, 32
	v_mov_b32_e32 v160, s9
	v_mov_b32_e32 v161, s11
	v_add_f32_e32 v160, s6, v160
	v_add_f32_e32 v161, s7, v161
	s_nop 0
	v_add_f32_e32 v160, v160, v161
	v_fmamk_f32 v160, v160, 0x3b800000, v252
	v_cmp_gt_f32_e32 vcc, s55, v160
	v_mul_f32_e32 v161, 0x4f800000, v160
	s_nop 0
	v_cndmask_b32_e32 v160, v160, v161, vcc
	v_sqrt_f32_e32 v161, v160
	s_nop 0
	v_add_u32_e32 v162, -1, v161
	v_fma_f32 v163, -v162, v161, v160
	v_cmp_ge_f32_e64 s[6:7], 0, v163
	v_add_u32_e32 v163, 1, v161
	s_nop 0
	v_cndmask_b32_e64 v162, v161, v162, s[6:7]
	v_fma_f32 v161, -v163, v161, v160
	v_cmp_lt_f32_e64 s[6:7], 0, v161
	s_nop 1
	v_cndmask_b32_e64 v161, v162, v163, s[6:7]
	v_mul_f32_e32 v162, 0x37800000, v161
	v_cndmask_b32_e32 v161, v161, v162, vcc
	v_cmp_class_f32_e32 vcc, v160, v253
	s_nop 1
	v_cndmask_b32_e32 v160, v161, v160, vcc
	v_div_scale_f32 v161, s[6:7], v160, v160, 1.0
	v_rcp_f32_e32 v162, v161
	s_nop 0
	v_fma_f32 v163, -v161, v162, 1.0
	v_fmac_f32_e32 v162, v163, v162
	v_div_scale_f32 v163, vcc, 1.0, v160, 1.0
	v_mul_f32_e32 v167, v163, v162
	v_fma_f32 v168, -v161, v167, v163
	v_fmac_f32_e32 v167, v168, v162
	v_fma_f32 v161, -v161, v167, v163
	v_div_fmas_f32 v161, v161, v162, v167
	v_div_fixup_f32 v160, v161, v160, 1.0
	v_lshlrev_b32_e32 v162, 16, v62
	v_and_b32_e32 v163, 0xffff0000, v62
	v_lshlrev_b32_e32 v62, 16, v63
	v_and_b32_e32 v63, 0xffff0000, v63
	v_mul_f32_e32 v154, v154, v160
	v_mul_f32_e32 v155, v155, v160
	v_mul_f32_e32 v152, v152, v160
	v_mul_f32_e32 v153, v153, v160
	s_nop 0
	v_mul_f32_e32 v62, v152, v62
	v_mul_f32_e32 v63, v153, v63
	v_mul_f32_e32 v152, v154, v162
	v_mul_f32_e32 v153, v155, v163
	s_nop 0
	v_cvt_pk_bf16_f32 v152, v152, v153
	v_cvt_pk_bf16_f32 v153, v62, v63
	v_add_f32_dpp v62, v164, v164 quad_perm:[1,0,3,2] row_mask:0xf bank_mask:0xf bound_ctrl:1
	global_store_dwordx2 v[70:71], v[152:153], off
	s_nop 0
	v_add_f32_dpp v62, v62, v62 quad_perm:[2,3,0,1] row_mask:0xf bank_mask:0xf bound_ctrl:1
	s_nop 1
	v_add_f32_dpp v62, v62, v62 row_half_mirror row_mask:0xf bank_mask:0xf bound_ctrl:1
	s_nop 1
	v_add_f32_dpp v62, v62, v62 row_mirror row_mask:0xf bank_mask:0xf bound_ctrl:1
	s_nop 0
	v_readlane_b32 s9, v62, 16
	v_readlane_b32 s11, v62, 48
	v_readlane_b32 s6, v62, 0
	v_readlane_b32 s7, v62, 32
	v_mov_b32_e32 v62, s9
	v_mov_b32_e32 v63, s11
	v_add_f32_e32 v62, s6, v62
	v_add_f32_e32 v63, s7, v63
	s_nop 0
	v_add_f32_e32 v62, v62, v63
	v_fmamk_f32 v62, v62, 0x3b800000, v252
	v_cmp_gt_f32_e32 vcc, s55, v62
	v_mul_f32_e32 v63, 0x4f800000, v62
	s_nop 0
	v_cndmask_b32_e32 v62, v62, v63, vcc
	v_sqrt_f32_e32 v63, v62
	s_nop 0
	v_add_u32_e32 v152, -1, v63
	v_fma_f32 v153, -v152, v63, v62
	v_cmp_ge_f32_e64 s[6:7], 0, v153
	v_add_u32_e32 v153, 1, v63
	s_nop 0
	v_cndmask_b32_e64 v152, v63, v152, s[6:7]
	v_fma_f32 v63, -v153, v63, v62
	v_cmp_lt_f32_e64 s[6:7], 0, v63
	s_nop 1
	v_cndmask_b32_e64 v63, v152, v153, s[6:7]
	v_mul_f32_e32 v152, 0x37800000, v63
	v_cndmask_b32_e32 v63, v63, v152, vcc
	v_cmp_class_f32_e32 vcc, v62, v253
	s_nop 1
	v_cndmask_b32_e32 v62, v63, v62, vcc
	v_div_scale_f32 v63, s[6:7], v62, v62, 1.0
	v_rcp_f32_e32 v152, v63
	s_nop 0
	v_fma_f32 v153, -v63, v152, 1.0
	v_fmac_f32_e32 v152, v153, v152
	v_div_scale_f32 v153, vcc, 1.0, v62, 1.0
	v_mul_f32_e32 v154, v153, v152
	v_fma_f32 v155, -v63, v154, v153
	v_fmac_f32_e32 v154, v155, v152
	v_fma_f32 v63, -v63, v154, v153
	v_div_fmas_f32 v63, v63, v152, v154
	v_div_fixup_f32 v62, v63, v62, 1.0
	v_lshlrev_b32_e32 v152, 16, v56
	v_and_b32_e32 v153, 0xffff0000, v56
	v_lshlrev_b32_e32 v56, 16, v57
	v_and_b32_e32 v57, 0xffff0000, v57
	v_mul_f32_e32 v150, v150, v62
	v_mul_f32_e32 v151, v151, v62
	v_mul_f32_e32 v63, v147, v62
	v_mul_f32_e32 v62, v146, v62
	s_nop 0
	v_mul_f32_e32 v56, v62, v56
	v_mul_f32_e32 v57, v63, v57
	v_mul_f32_e32 v62, v150, v152
	v_mul_f32_e32 v63, v151, v153
	s_nop 0
	v_cvt_pk_bf16_f32 v62, v62, v63
	v_cvt_pk_bf16_f32 v63, v56, v57
	v_add_f32_dpp v56, v165, v165 quad_perm:[1,0,3,2] row_mask:0xf bank_mask:0xf bound_ctrl:1
	global_store_dwordx2 v[70:71], v[62:63], off offset:512
	s_nop 0
	v_add_f32_dpp v56, v56, v56 quad_perm:[2,3,0,1] row_mask:0xf bank_mask:0xf bound_ctrl:1
	s_nop 1
	v_add_f32_dpp v56, v56, v56 row_half_mirror row_mask:0xf bank_mask:0xf bound_ctrl:1
	s_nop 1
	v_add_f32_dpp v56, v56, v56 row_mirror row_mask:0xf bank_mask:0xf bound_ctrl:1
	s_nop 0
	v_readlane_b32 s9, v56, 16
	v_readlane_b32 s11, v56, 48
	v_readlane_b32 s6, v56, 0
	v_readlane_b32 s7, v56, 32
	v_mov_b32_e32 v56, s9
	v_mov_b32_e32 v57, s11
	v_add_f32_e32 v56, s6, v56
	v_add_f32_e32 v57, s7, v57
	s_nop 0
	v_add_f32_e32 v56, v56, v57
	v_fmamk_f32 v56, v56, 0x3b800000, v252
	v_cmp_gt_f32_e32 vcc, s55, v56
	v_mul_f32_e32 v57, 0x4f800000, v56
	s_nop 0
	v_cndmask_b32_e32 v56, v56, v57, vcc
	v_sqrt_f32_e32 v57, v56
	s_nop 0
	v_add_u32_e32 v62, -1, v57
	v_fma_f32 v63, -v62, v57, v56
	v_cmp_ge_f32_e64 s[6:7], 0, v63
	v_add_u32_e32 v63, 1, v57
	s_nop 0
	v_cndmask_b32_e64 v62, v57, v62, s[6:7]
	v_fma_f32 v57, -v63, v57, v56
	v_cmp_lt_f32_e64 s[6:7], 0, v57
	s_nop 1
	v_cndmask_b32_e64 v57, v62, v63, s[6:7]
	v_mul_f32_e32 v62, 0x37800000, v57
	v_cndmask_b32_e32 v57, v57, v62, vcc
	v_cmp_class_f32_e32 vcc, v56, v253
	s_nop 1
	v_cndmask_b32_e32 v56, v57, v56, vcc
	v_div_scale_f32 v57, s[6:7], v56, v56, 1.0
	v_rcp_f32_e32 v62, v57
	s_nop 0
	v_fma_f32 v63, -v57, v62, 1.0
	v_fmac_f32_e32 v62, v63, v62
	v_div_scale_f32 v63, vcc, 1.0, v56, 1.0
	v_mul_f32_e32 v146, v63, v62
	v_fma_f32 v147, -v57, v146, v63
	v_fmac_f32_e32 v146, v147, v62
	v_fma_f32 v57, -v57, v146, v63
	v_div_fmas_f32 v57, v57, v62, v146
	v_div_fixup_f32 v56, v57, v56, 1.0
	v_lshlrev_b32_e32 v62, 16, v50
	v_and_b32_e32 v63, 0xffff0000, v50
	v_lshlrev_b32_e32 v50, 16, v51
	v_and_b32_e32 v51, 0xffff0000, v51
	v_mul_f32_e32 v140, v140, v56
	v_mul_f32_e32 v141, v141, v56
	v_mul_f32_e32 v57, v135, v56
	v_mul_f32_e32 v56, v134, v56
	s_nop 0
	v_mul_f32_e32 v50, v56, v50
	v_mul_f32_e32 v51, v57, v51
	v_mul_f32_e32 v56, v140, v62
	v_mul_f32_e32 v57, v141, v63
	s_nop 0
	v_cvt_pk_bf16_f32 v56, v56, v57
	v_cvt_pk_bf16_f32 v57, v50, v51
	v_add_f32_dpp v50, v166, v166 quad_perm:[1,0,3,2] row_mask:0xf bank_mask:0xf bound_ctrl:1
	global_store_dwordx2 v[70:71], v[56:57], off offset:1024
	s_nop 0
	v_add_f32_dpp v50, v50, v50 quad_perm:[2,3,0,1] row_mask:0xf bank_mask:0xf bound_ctrl:1
	s_nop 1
	v_add_f32_dpp v50, v50, v50 row_half_mirror row_mask:0xf bank_mask:0xf bound_ctrl:1
	s_nop 1
	v_add_f32_dpp v50, v50, v50 row_mirror row_mask:0xf bank_mask:0xf bound_ctrl:1
	s_nop 0
	v_readlane_b32 s9, v50, 16
	v_readlane_b32 s11, v50, 48
	v_readlane_b32 s6, v50, 0
	v_readlane_b32 s7, v50, 32
	v_mov_b32_e32 v50, s9
	v_mov_b32_e32 v51, s11
	v_add_f32_e32 v50, s6, v50
	v_add_f32_e32 v51, s7, v51
	s_nop 0
	v_add_f32_e32 v50, v50, v51
	v_fmamk_f32 v50, v50, 0x3b800000, v252
	v_cmp_gt_f32_e32 vcc, s55, v50
	v_mul_f32_e32 v51, 0x4f800000, v50
	s_nop 0
	v_cndmask_b32_e32 v50, v50, v51, vcc
	v_sqrt_f32_e32 v51, v50
	s_nop 0
	v_add_u32_e32 v56, -1, v51
	v_fma_f32 v57, -v56, v51, v50
	v_cmp_ge_f32_e64 s[6:7], 0, v57
	v_add_u32_e32 v57, 1, v51
	s_nop 0
	v_cndmask_b32_e64 v56, v51, v56, s[6:7]
	v_fma_f32 v51, -v57, v51, v50
	v_cmp_lt_f32_e64 s[6:7], 0, v51
	s_nop 1
	v_cndmask_b32_e64 v51, v56, v57, s[6:7]
	v_mul_f32_e32 v56, 0x37800000, v51
	v_cndmask_b32_e32 v51, v51, v56, vcc
	v_cmp_class_f32_e32 vcc, v50, v253
	s_nop 1
	v_cndmask_b32_e32 v50, v51, v50, vcc
	v_div_scale_f32 v51, s[6:7], v50, v50, 1.0
	v_rcp_f32_e32 v56, v51
	s_nop 0
	v_fma_f32 v57, -v51, v56, 1.0
	v_fmac_f32_e32 v56, v57, v56
	v_div_scale_f32 v57, vcc, 1.0, v50, 1.0
	v_mul_f32_e32 v62, v57, v56
	v_fma_f32 v63, -v51, v62, v57
	v_fmac_f32_e32 v62, v63, v56
	v_fma_f32 v51, -v51, v62, v57
	v_div_fmas_f32 v51, v51, v56, v62
	v_div_fixup_f32 v50, v51, v50, 1.0
	v_lshlrev_b32_e32 v56, 16, v44
	v_and_b32_e32 v57, 0xffff0000, v44
	v_lshlrev_b32_e32 v44, 16, v45
	v_and_b32_e32 v45, 0xffff0000, v45
	v_mul_f32_e32 v62, v88, v50
	v_mul_f32_e32 v63, v89, v50
	v_mul_f32_e32 v51, v87, v50
	v_mul_f32_e32 v50, v86, v50
	s_nop 0
	v_mul_f32_e32 v44, v50, v44
	v_mul_f32_e32 v45, v51, v45
	v_mul_f32_e32 v50, v62, v56
	v_mul_f32_e32 v51, v63, v57
	s_nop 0
	v_cvt_pk_bf16_f32 v50, v50, v51
	v_cvt_pk_bf16_f32 v51, v44, v45
	v_add_f32_dpp v44, v159, v159 quad_perm:[1,0,3,2] row_mask:0xf bank_mask:0xf bound_ctrl:1
	global_store_dwordx2 v[70:71], v[50:51], off offset:1536
	s_nop 0
	v_add_f32_dpp v44, v44, v44 quad_perm:[2,3,0,1] row_mask:0xf bank_mask:0xf bound_ctrl:1
	s_nop 1
	v_add_f32_dpp v44, v44, v44 row_half_mirror row_mask:0xf bank_mask:0xf bound_ctrl:1
	s_nop 1
	v_add_f32_dpp v44, v44, v44 row_mirror row_mask:0xf bank_mask:0xf bound_ctrl:1
	s_nop 0
	v_readlane_b32 s9, v44, 16
	v_readlane_b32 s11, v44, 48
	v_readlane_b32 s6, v44, 0
	v_readlane_b32 s7, v44, 32
	v_mov_b32_e32 v44, s9
	v_mov_b32_e32 v45, s11
	v_add_f32_e32 v44, s6, v44
	v_add_f32_e32 v45, s7, v45
	s_nop 0
	v_add_f32_e32 v44, v44, v45
	v_fmamk_f32 v44, v44, 0x3b800000, v252
	v_cmp_gt_f32_e32 vcc, s55, v44
	v_mul_f32_e32 v45, 0x4f800000, v44
	s_nop 0
	v_cndmask_b32_e32 v44, v44, v45, vcc
	v_sqrt_f32_e32 v45, v44
	s_nop 0
	v_add_u32_e32 v50, -1, v45
	v_fma_f32 v51, -v50, v45, v44
	v_cmp_ge_f32_e64 s[6:7], 0, v51
	v_add_u32_e32 v51, 1, v45
	s_nop 0
	v_cndmask_b32_e64 v50, v45, v50, s[6:7]
	v_fma_f32 v45, -v51, v45, v44
	v_cmp_lt_f32_e64 s[6:7], 0, v45
	s_nop 1
	v_cndmask_b32_e64 v45, v50, v51, s[6:7]
	v_mul_f32_e32 v50, 0x37800000, v45
	v_cndmask_b32_e32 v45, v45, v50, vcc
	v_cmp_class_f32_e32 vcc, v44, v253
	s_nop 1
	v_cndmask_b32_e32 v44, v45, v44, vcc
	v_div_scale_f32 v45, s[6:7], v44, v44, 1.0
	v_rcp_f32_e32 v50, v45
	s_nop 0
	v_fma_f32 v51, -v45, v50, 1.0
	v_fmac_f32_e32 v50, v51, v50
	v_div_scale_f32 v51, vcc, 1.0, v44, 1.0
	v_mul_f32_e32 v56, v51, v50
	v_fma_f32 v57, -v45, v56, v51
	v_fmac_f32_e32 v56, v57, v50
	v_fma_f32 v45, -v45, v56, v51
	v_div_fmas_f32 v45, v45, v50, v56
	v_div_fixup_f32 v44, v45, v44, 1.0
	v_lshlrev_b32_e32 v50, 16, v38
	v_and_b32_e32 v51, 0xffff0000, v38
	v_lshlrev_b32_e32 v38, 16, v39
	v_and_b32_e32 v39, 0xffff0000, v39
	v_mul_f32_e32 v56, v84, v44
	v_mul_f32_e32 v57, v85, v44
	v_mul_f32_e32 v45, v83, v44
	v_mul_f32_e32 v44, v82, v44
	s_nop 0
	v_mul_f32_e32 v38, v44, v38
	v_mul_f32_e32 v39, v45, v39
	v_mul_f32_e32 v44, v56, v50
	v_mul_f32_e32 v45, v57, v51
	s_nop 0
	v_cvt_pk_bf16_f32 v44, v44, v45
	v_cvt_pk_bf16_f32 v45, v38, v39
	v_add_f32_dpp v38, v158, v158 quad_perm:[1,0,3,2] row_mask:0xf bank_mask:0xf bound_ctrl:1
	global_store_dwordx2 v[70:71], v[44:45], off offset:2048
	s_nop 0
	v_add_f32_dpp v38, v38, v38 quad_perm:[2,3,0,1] row_mask:0xf bank_mask:0xf bound_ctrl:1
	s_nop 1
	v_add_f32_dpp v38, v38, v38 row_half_mirror row_mask:0xf bank_mask:0xf bound_ctrl:1
	s_nop 1
	v_add_f32_dpp v38, v38, v38 row_mirror row_mask:0xf bank_mask:0xf bound_ctrl:1
	s_nop 0
	v_readlane_b32 s9, v38, 16
	v_readlane_b32 s11, v38, 48
	v_readlane_b32 s6, v38, 0
	v_readlane_b32 s7, v38, 32
	v_mov_b32_e32 v38, s9
	v_mov_b32_e32 v39, s11
	v_add_f32_e32 v38, s6, v38
	v_add_f32_e32 v39, s7, v39
	s_nop 0
	v_add_f32_e32 v38, v38, v39
	v_fmamk_f32 v38, v38, 0x3b800000, v252
	v_cmp_gt_f32_e32 vcc, s55, v38
	v_mul_f32_e32 v39, 0x4f800000, v38
	s_nop 0
	v_cndmask_b32_e32 v38, v38, v39, vcc
	v_sqrt_f32_e32 v39, v38
	s_nop 0
	v_add_u32_e32 v44, -1, v39
	v_fma_f32 v45, -v44, v39, v38
	v_cmp_ge_f32_e64 s[6:7], 0, v45
	v_add_u32_e32 v45, 1, v39
	s_nop 0
	v_cndmask_b32_e64 v44, v39, v44, s[6:7]
	v_fma_f32 v39, -v45, v39, v38
	v_cmp_lt_f32_e64 s[6:7], 0, v39
	s_nop 1
	v_cndmask_b32_e64 v39, v44, v45, s[6:7]
	v_mul_f32_e32 v44, 0x37800000, v39
	v_cndmask_b32_e32 v39, v39, v44, vcc
	v_cmp_class_f32_e32 vcc, v38, v253
	s_nop 1
	v_cndmask_b32_e32 v38, v39, v38, vcc
	v_div_scale_f32 v39, s[6:7], v38, v38, 1.0
	v_rcp_f32_e32 v44, v39
	s_nop 0
	v_fma_f32 v45, -v39, v44, 1.0
	v_fmac_f32_e32 v44, v45, v44
	v_div_scale_f32 v45, vcc, 1.0, v38, 1.0
	v_mul_f32_e32 v50, v45, v44
	v_fma_f32 v51, -v39, v50, v45
	v_fmac_f32_e32 v50, v51, v44
	v_fma_f32 v39, -v39, v50, v45
	v_div_fmas_f32 v39, v39, v44, v50
	v_div_fixup_f32 v38, v39, v38, 1.0
	v_lshlrev_b32_e32 v44, 16, v34
	v_and_b32_e32 v45, 0xffff0000, v34
	v_lshlrev_b32_e32 v34, 16, v35
	v_and_b32_e32 v35, 0xffff0000, v35
	v_mul_f32_e32 v50, v80, v38
	v_mul_f32_e32 v51, v81, v38
	v_mul_f32_e32 v39, v79, v38
	v_mul_f32_e32 v38, v78, v38
	s_nop 0
	v_mul_f32_e32 v34, v38, v34
	v_mul_f32_e32 v35, v39, v35
	v_mul_f32_e32 v38, v50, v44
	v_mul_f32_e32 v39, v51, v45
	s_nop 0
	v_cvt_pk_bf16_f32 v38, v38, v39
	v_cvt_pk_bf16_f32 v39, v34, v35
	v_add_f32_dpp v34, v157, v157 quad_perm:[1,0,3,2] row_mask:0xf bank_mask:0xf bound_ctrl:1
	global_store_dwordx2 v[70:71], v[38:39], off offset:2560
	s_nop 0
	v_add_f32_dpp v34, v34, v34 quad_perm:[2,3,0,1] row_mask:0xf bank_mask:0xf bound_ctrl:1
	s_nop 1
	v_add_f32_dpp v34, v34, v34 row_half_mirror row_mask:0xf bank_mask:0xf bound_ctrl:1
	s_nop 1
	v_add_f32_dpp v34, v34, v34 row_mirror row_mask:0xf bank_mask:0xf bound_ctrl:1
	s_nop 0
	v_readlane_b32 s9, v34, 16
	v_readlane_b32 s11, v34, 48
	v_readlane_b32 s6, v34, 0
	v_readlane_b32 s7, v34, 32
	v_mov_b32_e32 v34, s9
	v_mov_b32_e32 v35, s11
	v_add_f32_e32 v34, s6, v34
	v_add_f32_e32 v35, s7, v35
	s_nop 0
	v_add_f32_e32 v34, v34, v35
	v_fmamk_f32 v34, v34, 0x3b800000, v252
	v_cmp_gt_f32_e32 vcc, s55, v34
	v_mul_f32_e32 v35, 0x4f800000, v34
	s_nop 0
	v_cndmask_b32_e32 v34, v34, v35, vcc
	v_sqrt_f32_e32 v35, v34
	s_nop 0
	v_add_u32_e32 v38, -1, v35
	v_fma_f32 v39, -v38, v35, v34
	v_cmp_ge_f32_e64 s[6:7], 0, v39
	v_add_u32_e32 v39, 1, v35
	s_nop 0
	v_cndmask_b32_e64 v38, v35, v38, s[6:7]
	v_fma_f32 v35, -v39, v35, v34
	v_cmp_lt_f32_e64 s[6:7], 0, v35
	s_nop 1
	v_cndmask_b32_e64 v35, v38, v39, s[6:7]
	v_mul_f32_e32 v38, 0x37800000, v35
	v_cndmask_b32_e32 v35, v35, v38, vcc
	v_cmp_class_f32_e32 vcc, v34, v253
	s_nop 1
	v_cndmask_b32_e32 v34, v35, v34, vcc
	v_div_scale_f32 v35, s[6:7], v34, v34, 1.0
	v_rcp_f32_e32 v38, v35
	s_nop 0
	v_fma_f32 v39, -v35, v38, 1.0
	v_fmac_f32_e32 v38, v39, v38
	v_div_scale_f32 v39, vcc, 1.0, v34, 1.0
	v_mul_f32_e32 v44, v39, v38
	v_fma_f32 v45, -v35, v44, v39
	v_fmac_f32_e32 v44, v45, v38
	v_fma_f32 v35, -v35, v44, v39
	v_div_fmas_f32 v35, v35, v38, v44
	v_div_fixup_f32 v34, v35, v34, 1.0
	v_lshlrev_b32_e32 v38, 16, v30
	v_and_b32_e32 v39, 0xffff0000, v30
	v_lshlrev_b32_e32 v30, 16, v31
	v_and_b32_e32 v31, 0xffff0000, v31
	v_mul_f32_e32 v44, v76, v34
	v_mul_f32_e32 v45, v77, v34
	v_mul_f32_e32 v35, v75, v34
	v_mul_f32_e32 v34, v74, v34
	s_nop 0
	v_mul_f32_e32 v30, v34, v30
; template <bool HG>
; __device__ __forceinline__ void readout_phase2(const Args& a, Frame& F, const float* gain, int nrows) {
;     ...
;     const bool cx = ML + nw < nrows;
;     RO_LOAD(f2, b2, g2, cx ? ML + nw : nw + 7 * 2048);
	v_mul_f32_e32 v31, v35, v31
	v_mul_f32_e32 v34, v44, v38
	v_mul_f32_e32 v35, v45, v39
	s_nop 0
	v_cvt_pk_bf16_f32 v34, v34, v35
	v_cvt_pk_bf16_f32 v35, v30, v31
	v_add_f32_dpp v30, v156, v156 quad_perm:[1,0,3,2] row_mask:0xf bank_mask:0xf bound_ctrl:1
	global_store_dwordx2 v[70:71], v[34:35], off offset:3072
	s_nop 0
	v_add_f32_dpp v30, v30, v30 quad_perm:[2,3,0,1] row_mask:0xf bank_mask:0xf bound_ctrl:1
	s_nop 1
	v_add_f32_dpp v30, v30, v30 row_half_mirror row_mask:0xf bank_mask:0xf bound_ctrl:1
	s_nop 1
	v_add_f32_dpp v30, v30, v30 row_mirror row_mask:0xf bank_mask:0xf bound_ctrl:1
	s_nop 0
	v_readlane_b32 s9, v30, 16
	v_readlane_b32 s11, v30, 48
	v_readlane_b32 s6, v30, 0
	v_readlane_b32 s7, v30, 32
	v_mov_b32_e32 v30, s9
	v_mov_b32_e32 v31, s11
	v_add_f32_e32 v30, s6, v30
	v_add_f32_e32 v31, s7, v31
	s_nop 0
	v_add_f32_e32 v30, v30, v31
	v_fmamk_f32 v30, v30, 0x3b800000, v252
	v_cmp_gt_f32_e32 vcc, s55, v30
	v_mul_f32_e32 v31, 0x4f800000, v30
	s_nop 0
	v_cndmask_b32_e32 v30, v30, v31, vcc
	v_sqrt_f32_e32 v31, v30
	s_nop 0
	v_add_u32_e32 v34, -1, v31
	v_fma_f32 v35, -v34, v31, v30
	v_cmp_ge_f32_e64 s[6:7], 0, v35
	v_add_u32_e32 v35, 1, v31
	s_nop 0
	v_cndmask_b32_e64 v34, v31, v34, s[6:7]
	v_fma_f32 v31, -v35, v31, v30
	v_cmp_lt_f32_e64 s[6:7], 0, v31
	s_nop 1
	v_cndmask_b32_e64 v31, v34, v35, s[6:7]
	v_mul_f32_e32 v34, 0x37800000, v31
	v_cndmask_b32_e32 v31, v31, v34, vcc
	v_cmp_class_f32_e32 vcc, v30, v253
	s_nop 1
	v_cndmask_b32_e32 v30, v31, v30, vcc
	v_div_scale_f32 v31, s[6:7], v30, v30, 1.0
	v_rcp_f32_e32 v34, v31
	s_cselect_b32 s6, s82, s10
	s_ashr_i32 s7, s6, 31
	s_lshl_b64 s[48:49], s[6:7], 12
	v_fma_f32 v35, -v31, v34, 1.0
	v_fmac_f32_e32 v34, v35, v34
	v_div_scale_f32 v35, vcc, 1.0, v30, 1.0
	v_mul_f32_e32 v38, v35, v34
	v_fma_f32 v39, -v31, v38, v35
	v_fmac_f32_e32 v38, v39, v34
	v_fma_f32 v31, -v31, v38, v35
	v_div_fmas_f32 v31, v31, v34, v38
	v_div_fixup_f32 v30, v31, v30, 1.0
	s_waitcnt vmcnt(62)
	v_lshlrev_b32_e32 v34, 16, v26
	v_and_b32_e32 v35, 0xffff0000, v26
	v_lshlrev_b32_e32 v26, 16, v27
	v_and_b32_e32 v27, 0xffff0000, v27
	v_mul_f32_e32 v38, v72, v30
	v_mul_f32_e32 v39, v73, v30
	v_mul_f32_e32 v31, v69, v30
	v_mul_f32_e32 v30, v68, v30
	v_lshl_add_u64 v[6:7], v[6:7], 0, s[48:49]
	v_mul_f32_e32 v26, v30, v26
	v_mul_f32_e32 v27, v31, v27
	v_mul_f32_e32 v30, v38, v34
	v_mul_f32_e32 v31, v39, v35
	v_lshl_add_u64 v[4:5], v[4:5], 0, s[48:49]
	v_cvt_pk_bf16_f32 v30, v30, v31
	v_cvt_pk_bf16_f32 v31, v26, v27
	global_store_dwordx2 v[70:71], v[30:31], off offset:3584
	v_lshlrev_b32_e32 v26, 16, v148
	v_and_b32_e32 v27, 0xffff0000, v148
	s_waitcnt vmcnt(62)
	v_lshlrev_b32_e32 v30, 16, v142
	v_and_b32_e32 v31, 0xffff0000, v142
	v_add_f32_e32 v140, v26, v30
	v_add_f32_e32 v141, v27, v31
	v_lshlrev_b32_e32 v26, 16, v149
	v_and_b32_e32 v27, 0xffff0000, v149
	v_lshlrev_b32_e32 v30, 16, v143
	v_and_b32_e32 v31, 0xffff0000, v143
	v_add_f32_e32 v142, v26, v30
	v_add_f32_e32 v143, v27, v31
	v_mov_b32_e32 v30, v141
	v_mov_b32_e32 v31, v143
	v_mov_b32_e32 v26, v140
	v_mov_b32_e32 v27, v142
	v_mul_f32_e32 v30, v30, v30
	v_mul_f32_e32 v31, v31, v31
	v_lshl_add_u64 v[4:5], v[4:5], 0, v[0:1]
	v_fma_f32 v26, v26, v26, v30
	v_fma_f32 v27, v27, v27, v31
	s_waitcnt vmcnt(59)
	v_lshlrev_b32_e32 v30, 16, v130
	v_add_f32_e32 v34, v26, v27
	v_lshlrev_b32_e32 v26, 16, v136
	v_and_b32_e32 v27, 0xffff0000, v136
	v_and_b32_e32 v31, 0xffff0000, v130
	v_add_f32_e32 v134, v26, v30
	v_add_f32_e32 v135, v27, v31
	v_lshlrev_b32_e32 v26, 16, v137
	v_and_b32_e32 v27, 0xffff0000, v137
	v_lshlrev_b32_e32 v30, 16, v131
	v_and_b32_e32 v31, 0xffff0000, v131
	v_add_f32_e32 v136, v26, v30
	v_add_f32_e32 v137, v27, v31
	v_mov_b32_e32 v30, v135
	v_mov_b32_e32 v31, v137
	v_mov_b32_e32 v26, v134
	v_mov_b32_e32 v27, v136
	v_mul_f32_e32 v30, v30, v30
	v_mul_f32_e32 v31, v31, v31
	s_cmp_ge_i32 s82, s47
	v_fma_f32 v26, v26, v26, v30
	v_fma_f32 v27, v27, v27, v31
	s_waitcnt vmcnt(56)
	v_lshlrev_b32_e32 v30, 16, v122
	v_add_f32_e32 v35, v26, v27
	v_lshlrev_b32_e32 v26, 16, v126
	v_and_b32_e32 v27, 0xffff0000, v126
	v_and_b32_e32 v31, 0xffff0000, v122
	v_add_f32_e32 v130, v26, v30
	v_add_f32_e32 v131, v27, v31
	v_lshlrev_b32_e32 v26, 16, v127
	v_and_b32_e32 v27, 0xffff0000, v127
	v_lshlrev_b32_e32 v30, 16, v123
	v_and_b32_e32 v31, 0xffff0000, v123
	v_add_f32_e32 v122, v26, v30
	v_add_f32_e32 v123, v27, v31
	v_mov_b32_e32 v30, v131
	v_mov_b32_e32 v31, v123
	v_mov_b32_e32 v26, v130
	v_mov_b32_e32 v27, v122
	v_mul_f32_e32 v30, v30, v30
	v_mul_f32_e32 v31, v31, v31
	s_nop 0
	v_fma_f32 v26, v26, v26, v30
	v_fma_f32 v27, v27, v27, v31
	s_waitcnt vmcnt(53)
	v_lshlrev_b32_e32 v30, 16, v118
	v_add_f32_e32 v38, v26, v27
	v_lshlrev_b32_e32 v26, 16, v114
	v_and_b32_e32 v27, 0xffff0000, v114
	v_and_b32_e32 v31, 0xffff0000, v118
	v_add_f32_e32 v86, v26, v30
	v_add_f32_e32 v87, v27, v31
	v_lshlrev_b32_e32 v26, 16, v115
	v_and_b32_e32 v27, 0xffff0000, v115
	v_lshlrev_b32_e32 v30, 16, v119
	v_and_b32_e32 v31, 0xffff0000, v119
	v_add_f32_e32 v88, v26, v30
	v_add_f32_e32 v89, v27, v31
	v_mov_b32_e32 v30, v87
	v_mov_b32_e32 v31, v89
	v_mov_b32_e32 v26, v86
	v_mov_b32_e32 v27, v88
	v_mul_f32_e32 v30, v30, v30
	v_mul_f32_e32 v31, v31, v31
	s_nop 0
	v_fma_f32 v26, v26, v26, v30
	v_fma_f32 v27, v27, v27, v31
	s_waitcnt vmcnt(50)
	v_lshlrev_b32_e32 v30, 16, v106
	v_add_f32_e32 v39, v26, v27
	v_lshlrev_b32_e32 v26, 16, v110
	v_and_b32_e32 v27, 0xffff0000, v110
	v_and_b32_e32 v31, 0xffff0000, v106
	v_add_f32_e32 v78, v26, v30
	v_add_f32_e32 v79, v27, v31
	v_lshlrev_b32_e32 v26, 16, v111
	v_and_b32_e32 v27, 0xffff0000, v111
	v_lshlrev_b32_e32 v30, 16, v107
	v_and_b32_e32 v31, 0xffff0000, v107
	v_add_f32_e32 v80, v26, v30
	v_add_f32_e32 v81, v27, v31
	v_mov_b32_e32 v30, v79
	v_mov_b32_e32 v31, v81
	v_mov_b32_e32 v26, v78
	v_mov_b32_e32 v27, v80
	v_mul_f32_e32 v30, v30, v30
	v_mul_f32_e32 v31, v31, v31
	s_nop 0
	v_fma_f32 v26, v26, v26, v30
	v_fma_f32 v27, v27, v27, v31
	s_waitcnt vmcnt(47)
	v_lshlrev_b32_e32 v30, 16, v98
	v_add_f32_e32 v56, v26, v27
	v_lshlrev_b32_e32 v26, 16, v102
	v_and_b32_e32 v27, 0xffff0000, v102
	v_and_b32_e32 v31, 0xffff0000, v98
	v_add_f32_e32 v70, v26, v30
	v_add_f32_e32 v71, v27, v31
	v_lshlrev_b32_e32 v26, 16, v103
	v_and_b32_e32 v27, 0xffff0000, v103
	v_lshlrev_b32_e32 v30, 16, v99
	v_and_b32_e32 v31, 0xffff0000, v99
	v_add_f32_e32 v72, v26, v30
	v_add_f32_e32 v73, v27, v31
	v_mov_b32_e32 v30, v71
	v_mov_b32_e32 v31, v73
	v_mov_b32_e32 v26, v70
	v_mov_b32_e32 v27, v72
	v_mul_f32_e32 v30, v30, v30
	v_mul_f32_e32 v31, v31, v31
	s_nop 0
	v_fma_f32 v26, v26, v26, v30
	v_fma_f32 v27, v27, v27, v31
	s_waitcnt vmcnt(44)
	v_lshlrev_b32_e32 v30, 16, v90
	v_add_f32_e32 v57, v26, v27
	v_lshlrev_b32_e32 v26, 16, v94
	v_and_b32_e32 v27, 0xffff0000, v94
	v_and_b32_e32 v31, 0xffff0000, v90
	v_add_f32_e32 v62, v26, v30
	v_add_f32_e32 v63, v27, v31
	v_lshlrev_b32_e32 v26, 16, v95
	v_and_b32_e32 v27, 0xffff0000, v95
	v_lshlrev_b32_e32 v30, 16, v91
	v_and_b32_e32 v31, 0xffff0000, v91
	v_add_f32_e32 v68, v26, v30
	v_add_f32_e32 v69, v27, v31
	v_mov_b32_e32 v30, v63
	v_mov_b32_e32 v31, v69
	v_mov_b32_e32 v26, v62
	v_mov_b32_e32 v27, v68
	v_mul_f32_e32 v30, v30, v30
	v_mul_f32_e32 v31, v31, v31
	s_nop 0
	v_fma_f32 v26, v26, v26, v30
	v_fma_f32 v27, v27, v27, v31
	s_waitcnt vmcnt(41)
	v_lshlrev_b32_e32 v30, 16, v64
	v_add_f32_e32 v74, v26, v27
	v_lshlrev_b32_e32 v26, 16, v58
	v_and_b32_e32 v27, 0xffff0000, v58
	v_and_b32_e32 v31, 0xffff0000, v64
	v_add_f32_e32 v44, v26, v30
	v_add_f32_e32 v45, v27, v31
	v_lshlrev_b32_e32 v26, 16, v59
	v_and_b32_e32 v27, 0xffff0000, v59
	v_lshlrev_b32_e32 v30, 16, v65
	v_and_b32_e32 v31, 0xffff0000, v65
	v_add_f32_e32 v50, v26, v30
	v_add_f32_e32 v51, v27, v31
	v_mov_b32_e32 v30, v45
	v_mov_b32_e32 v31, v51
	v_mov_b32_e32 v26, v44
	v_mov_b32_e32 v27, v50
	v_mul_f32_e32 v30, v30, v30
	v_mul_f32_e32 v31, v31, v31
	s_nop 0
	v_fma_f32 v26, v26, v26, v30
	v_fma_f32 v27, v27, v27, v31
	s_waitcnt vmcnt(30)
	v_and_b32_e32 v31, 0xffff0000, v138
	v_add_f32_e32 v30, v26, v27
	v_add_f32_dpp v26, v34, v34 quad_perm:[1,0,3,2] row_mask:0xf bank_mask:0xf bound_ctrl:1
	s_nop 1
	v_add_f32_dpp v26, v26, v26 quad_perm:[2,3,0,1] row_mask:0xf bank_mask:0xf bound_ctrl:1
	s_nop 1
	v_add_f32_dpp v26, v26, v26 row_half_mirror row_mask:0xf bank_mask:0xf bound_ctrl:1
	s_nop 1
	v_add_f32_dpp v26, v26, v26 row_mirror row_mask:0xf bank_mask:0xf bound_ctrl:1
	s_nop 0
	v_readlane_b32 s8, v26, 16
	v_readlane_b32 s9, v26, 48
	v_readlane_b32 s6, v26, 0
	v_readlane_b32 s7, v26, 32
	v_mov_b32_e32 v26, s8
	v_mov_b32_e32 v27, s9
	v_add_f32_e32 v26, s6, v26
	v_add_f32_e32 v27, s7, v27
	s_nop 0
	v_add_f32_e32 v26, v26, v27
	v_fmamk_f32 v26, v26, 0x3b800000, v252
	v_cmp_gt_f32_e32 vcc, s55, v26
	v_mul_f32_e32 v27, 0x4f800000, v26
	s_nop 0
	v_cndmask_b32_e32 v211, v26, v27, vcc
	v_add_f32_dpp v26, v35, v35 quad_perm:[1,0,3,2] row_mask:0xf bank_mask:0xf bound_ctrl:1
	v_sqrt_f32_e32 v214, v211
	s_nop 0
	v_add_f32_dpp v26, v26, v26 quad_perm:[2,3,0,1] row_mask:0xf bank_mask:0xf bound_ctrl:1
	v_add_u32_e32 v216, -1, v214
	s_nop 0
	v_add_f32_dpp v26, v26, v26 row_half_mirror row_mask:0xf bank_mask:0xf bound_ctrl:1
	v_add_u32_e32 v213, 1, v214
	v_fma_f32 v178, -v216, v214, v211
	v_add_f32_dpp v26, v26, v26 row_mirror row_mask:0xf bank_mask:0xf bound_ctrl:1
	v_fma_f32 v179, -v213, v214, v211
	v_readlane_b32 s8, v26, 16
	v_readlane_b32 s9, v26, 48
	v_readlane_b32 s6, v26, 0
	v_readlane_b32 s7, v26, 32
	v_mov_b32_e32 v26, s8
	v_mov_b32_e32 v27, s9
	v_add_f32_e32 v26, s6, v26
	v_add_f32_e32 v27, s7, v27
	s_nop 0
	v_add_f32_e32 v26, v26, v27
	v_fmamk_f32 v26, v26, 0x3b800000, v252
	v_cmp_gt_f32_e64 s[30:31], s55, v26
	v_mul_f32_e32 v27, 0x4f800000, v26
	s_nop 0
	v_cndmask_b32_e64 v202, v26, v27, s[30:31]
	v_add_f32_dpp v26, v38, v38 quad_perm:[1,0,3,2] row_mask:0xf bank_mask:0xf bound_ctrl:1
	v_sqrt_f32_e32 v205, v202
	s_nop 0
	v_add_f32_dpp v26, v26, v26 quad_perm:[2,3,0,1] row_mask:0xf bank_mask:0xf bound_ctrl:1
	v_add_u32_e32 v209, -1, v205
	s_nop 0
	v_add_f32_dpp v26, v26, v26 row_half_mirror row_mask:0xf bank_mask:0xf bound_ctrl:1
	v_add_u32_e32 v207, 1, v205
	s_nop 0
	v_add_f32_dpp v26, v26, v26 row_mirror row_mask:0xf bank_mask:0xf bound_ctrl:1
	s_nop 0
	v_readlane_b32 s8, v26, 16
	v_readlane_b32 s9, v26, 48
	v_readlane_b32 s6, v26, 0
	v_readlane_b32 s7, v26, 32
	v_mov_b32_e32 v26, s8
	v_mov_b32_e32 v27, s9
	v_add_f32_e32 v26, s6, v26
	v_add_f32_e32 v27, s7, v27
	s_nop 0
	v_add_f32_e32 v26, v26, v27
	v_fmamk_f32 v26, v26, 0x3b800000, v252
	v_cmp_gt_f32_e64 s[26:27], s55, v26
	v_mul_f32_e32 v27, 0x4f800000, v26
	s_nop 0
	v_cndmask_b32_e64 v194, v26, v27, s[26:27]
	v_add_f32_dpp v26, v39, v39 quad_perm:[1,0,3,2] row_mask:0xf bank_mask:0xf bound_ctrl:1
	v_sqrt_f32_e32 v197, v194
	s_nop 0
	v_add_f32_dpp v26, v26, v26 quad_perm:[2,3,0,1] row_mask:0xf bank_mask:0xf bound_ctrl:1
	v_add_u32_e32 v199, -1, v197
	s_nop 0
	v_add_f32_dpp v26, v26, v26 row_half_mirror row_mask:0xf bank_mask:0xf bound_ctrl:1
	v_add_u32_e32 v196, 1, v197
	s_nop 0
	v_add_f32_dpp v26, v26, v26 row_mirror row_mask:0xf bank_mask:0xf bound_ctrl:1
	s_nop 0
	v_readlane_b32 s8, v26, 16
	v_readlane_b32 s9, v26, 48
	v_readlane_b32 s6, v26, 0
	v_readlane_b32 s7, v26, 32
	v_mov_b32_e32 v26, s8
	v_mov_b32_e32 v27, s9
	v_add_f32_e32 v26, s6, v26
	v_add_f32_e32 v27, s7, v27
	s_nop 0
	v_add_f32_e32 v26, v26, v27
	v_fmamk_f32 v26, v26, 0x3b800000, v252
	v_cmp_gt_f32_e64 s[22:23], s55, v26
	v_mul_f32_e32 v27, 0x4f800000, v26
	s_nop 0
	v_cndmask_b32_e64 v186, v26, v27, s[22:23]
	v_add_f32_dpp v26, v56, v56 quad_perm:[1,0,3,2] row_mask:0xf bank_mask:0xf bound_ctrl:1
	v_sqrt_f32_e32 v189, v186
	s_nop 0
	v_add_f32_dpp v26, v26, v26 quad_perm:[2,3,0,1] row_mask:0xf bank_mask:0xf bound_ctrl:1
	v_add_u32_e32 v193, -1, v189
	s_nop 0
	v_add_f32_dpp v26, v26, v26 row_half_mirror row_mask:0xf bank_mask:0xf bound_ctrl:1
	v_add_u32_e32 v191, 1, v189
	s_nop 0
	v_add_f32_dpp v26, v26, v26 row_mirror row_mask:0xf bank_mask:0xf bound_ctrl:1
	s_nop 0
	v_readlane_b32 s8, v26, 16
	v_readlane_b32 s9, v26, 48
	v_readlane_b32 s6, v26, 0
	v_readlane_b32 s7, v26, 32
	v_mov_b32_e32 v26, s8
	v_mov_b32_e32 v27, s9
	v_add_f32_e32 v26, s6, v26
	v_add_f32_e32 v27, s7, v27
	s_nop 0
	v_add_f32_e32 v26, v26, v27
	v_fmamk_f32 v26, v26, 0x3b800000, v252
	v_cmp_gt_f32_e64 s[18:19], s55, v26
	v_mul_f32_e32 v27, 0x4f800000, v26
	s_nop 0
	v_cndmask_b32_e64 v172, v26, v27, s[18:19]
	v_add_f32_dpp v26, v57, v57 quad_perm:[1,0,3,2] row_mask:0xf bank_mask:0xf bound_ctrl:1
	v_sqrt_f32_e32 v175, v172
	s_nop 0
	v_add_f32_dpp v26, v26, v26 quad_perm:[2,3,0,1] row_mask:0xf bank_mask:0xf bound_ctrl:1
	v_add_u32_e32 v177, -1, v175
	s_nop 0
	v_add_f32_dpp v26, v26, v26 row_half_mirror row_mask:0xf bank_mask:0xf bound_ctrl:1
	v_add_u32_e32 v174, 1, v175
	s_nop 0
	v_add_f32_dpp v26, v26, v26 row_mirror row_mask:0xf bank_mask:0xf bound_ctrl:1
	s_nop 0
	v_readlane_b32 s8, v26, 16
	v_readlane_b32 s9, v26, 48
	v_readlane_b32 s6, v26, 0
	v_readlane_b32 s7, v26, 32
	v_mov_b32_e32 v26, s8
	v_mov_b32_e32 v27, s9
	v_add_f32_e32 v26, s6, v26
	v_add_f32_e32 v27, s7, v27
	s_nop 0
	v_add_f32_e32 v26, v26, v27
	v_fmamk_f32 v26, v26, 0x3b800000, v252
	v_cmp_gt_f32_e64 s[14:15], s55, v26
	v_mul_f32_e32 v27, 0x4f800000, v26
	s_nop 0
	v_cndmask_b32_e64 v164, v26, v27, s[14:15]
	v_add_f32_dpp v26, v74, v74 quad_perm:[1,0,3,2] row_mask:0xf bank_mask:0xf bound_ctrl:1
	v_sqrt_f32_e32 v167, v164
	s_nop 0
	v_add_f32_dpp v26, v26, v26 quad_perm:[2,3,0,1] row_mask:0xf bank_mask:0xf bound_ctrl:1
	v_add_u32_e32 v171, -1, v167
	s_nop 0
	v_add_f32_dpp v26, v26, v26 row_half_mirror row_mask:0xf bank_mask:0xf bound_ctrl:1
	v_add_u32_e32 v169, 1, v167
	s_nop 0
	v_add_f32_dpp v26, v26, v26 row_mirror row_mask:0xf bank_mask:0xf bound_ctrl:1
	s_nop 0
	v_readlane_b32 s8, v26, 16
	v_readlane_b32 s9, v26, 48
	v_readlane_b32 s6, v26, 0
	v_readlane_b32 s7, v26, 32
	v_mov_b32_e32 v26, s8
	v_mov_b32_e32 v27, s9
	v_add_f32_e32 v26, s6, v26
	v_add_f32_e32 v27, s7, v27
	s_nop 0
	v_add_f32_e32 v26, v26, v27
	v_fmamk_f32 v26, v26, 0x3b800000, v252
	v_cmp_gt_f32_e64 s[10:11], s55, v26
	v_mul_f32_e32 v27, 0x4f800000, v26
	s_nop 0
	v_cndmask_b32_e64 v156, v26, v27, s[10:11]
	v_add_f32_dpp v26, v30, v30 quad_perm:[1,0,3,2] row_mask:0xf bank_mask:0xf bound_ctrl:1
	v_lshlrev_b32_e32 v30, 16, v138
	v_sqrt_f32_e32 v159, v156
	v_add_f32_dpp v26, v26, v26 quad_perm:[2,3,0,1] row_mask:0xf bank_mask:0xf bound_ctrl:1
	v_add_u32_e32 v161, -1, v159
	s_nop 0
	v_add_f32_dpp v26, v26, v26 row_half_mirror row_mask:0xf bank_mask:0xf bound_ctrl:1
	v_add_u32_e32 v158, 1, v159
	s_nop 0
	v_add_f32_dpp v26, v26, v26 row_mirror row_mask:0xf bank_mask:0xf bound_ctrl:1
	s_nop 0
	v_readlane_b32 s8, v26, 16
	v_readlane_b32 s9, v26, 48
	v_readlane_b32 s6, v26, 0
	v_readlane_b32 s7, v26, 32
	v_mov_b32_e32 v26, s8
	v_mov_b32_e32 v27, s9
	v_add_f32_e32 v26, s6, v26
	v_add_f32_e32 v27, s7, v27
	s_nop 0
	v_add_f32_e32 v26, v26, v27
	v_fmamk_f32 v26, v26, 0x3b800000, v252
	v_cmp_gt_f32_e64 s[6:7], s55, v26
	v_mul_f32_e32 v27, 0x4f800000, v26
	s_nop 0
	v_cndmask_b32_e64 v150, v26, v27, s[6:7]
	v_lshlrev_b32_e32 v26, 16, v144
	v_and_b32_e32 v27, 0xffff0000, v144
	v_add_f32_e32 v126, v26, v30
	v_add_f32_e32 v127, v27, v31
	v_lshlrev_b32_e32 v26, 16, v145
	v_and_b32_e32 v27, 0xffff0000, v145
	v_lshlrev_b32_e32 v30, 16, v139
	v_and_b32_e32 v31, 0xffff0000, v139
	v_add_f32_e32 v138, v26, v30
	v_add_f32_e32 v139, v27, v31
	v_mov_b32_e32 v30, v127
	v_mov_b32_e32 v31, v139
	v_mov_b32_e32 v26, v126
	v_mov_b32_e32 v27, v138
	v_mul_f32_e32 v30, v30, v30
	v_mul_f32_e32 v31, v31, v31
	v_sqrt_f32_e32 v151, v150
	v_fma_f32 v26, v26, v26, v30
	v_fma_f32 v27, v27, v27, v31
	s_waitcnt vmcnt(27)
	v_lshlrev_b32_e32 v30, 16, v128
	v_add_f32_e32 v34, v26, v27
	v_lshlrev_b32_e32 v26, 16, v132
	v_and_b32_e32 v27, 0xffff0000, v132
	v_and_b32_e32 v31, 0xffff0000, v128
	v_add_f32_e32 v114, v26, v30
	v_add_f32_e32 v115, v27, v31
	v_lshlrev_b32_e32 v26, 16, v133
	v_and_b32_e32 v27, 0xffff0000, v133
	v_lshlrev_b32_e32 v30, 16, v129
	v_and_b32_e32 v31, 0xffff0000, v129
	v_add_f32_e32 v118, v26, v30
	v_add_f32_e32 v119, v27, v31
	v_mov_b32_e32 v30, v115
	v_mov_b32_e32 v31, v119
	v_mov_b32_e32 v26, v114
	v_mov_b32_e32 v27, v118
	v_mul_f32_e32 v30, v30, v30
	v_mul_f32_e32 v31, v31, v31
	v_add_u32_e32 v155, -1, v151
	v_fma_f32 v26, v26, v26, v30
	v_fma_f32 v27, v27, v27, v31
	s_waitcnt vmcnt(24)
	v_lshlrev_b32_e32 v30, 16, v120
	v_add_f32_e32 v35, v26, v27
	v_lshlrev_b32_e32 v26, 16, v124
	v_and_b32_e32 v27, 0xffff0000, v124
	v_and_b32_e32 v31, 0xffff0000, v120
	v_add_f32_e32 v102, v26, v30
	v_add_f32_e32 v103, v27, v31
	v_lshlrev_b32_e32 v26, 16, v125
	v_and_b32_e32 v27, 0xffff0000, v125
	v_lshlrev_b32_e32 v30, 16, v121
	v_and_b32_e32 v31, 0xffff0000, v121
	v_add_f32_e32 v106, v26, v30
	v_add_f32_e32 v107, v27, v31
	v_mov_b32_e32 v30, v103
	v_mov_b32_e32 v31, v107
	v_mov_b32_e32 v26, v102
	v_mov_b32_e32 v27, v106
	v_mul_f32_e32 v30, v30, v30
	v_mul_f32_e32 v31, v31, v31
	v_add_u32_e32 v153, 1, v151
	v_fma_f32 v26, v26, v26, v30
	v_fma_f32 v27, v27, v27, v31
	s_waitcnt vmcnt(21)
	v_lshlrev_b32_e32 v30, 16, v116
	v_add_f32_e32 v38, v26, v27
	v_lshlrev_b32_e32 v26, 16, v112
	v_and_b32_e32 v27, 0xffff0000, v112
	v_and_b32_e32 v31, 0xffff0000, v116
	v_add_f32_e32 v90, v26, v30
	v_add_f32_e32 v91, v27, v31
	v_lshlrev_b32_e32 v26, 16, v113
	v_and_b32_e32 v27, 0xffff0000, v113
	v_lshlrev_b32_e32 v30, 16, v117
	v_and_b32_e32 v31, 0xffff0000, v117
	v_add_f32_e32 v94, v26, v30
	v_add_f32_e32 v95, v27, v31
	v_mov_b32_e32 v30, v91
	v_mov_b32_e32 v31, v95
	v_mov_b32_e32 v26, v90
	v_mov_b32_e32 v27, v94
	v_mul_f32_e32 v30, v30, v30
	v_mul_f32_e32 v31, v31, v31
	s_nop 0
	v_fma_f32 v26, v26, v26, v30
	v_fma_f32 v27, v27, v27, v31
	s_waitcnt vmcnt(18)
	v_lshlrev_b32_e32 v30, 16, v104
	v_add_f32_e32 v39, v26, v27
	v_lshlrev_b32_e32 v26, 16, v108
	v_and_b32_e32 v27, 0xffff0000, v108
	v_and_b32_e32 v31, 0xffff0000, v104
	v_add_f32_e32 v82, v26, v30
	v_add_f32_e32 v83, v27, v31
	v_lshlrev_b32_e32 v26, 16, v109
	v_and_b32_e32 v27, 0xffff0000, v109
	v_lshlrev_b32_e32 v30, 16, v105
	v_and_b32_e32 v31, 0xffff0000, v105
	v_add_f32_e32 v84, v26, v30
	v_add_f32_e32 v85, v27, v31
	v_mov_b32_e32 v30, v83
	v_mov_b32_e32 v31, v85
	v_mov_b32_e32 v26, v82
	v_mov_b32_e32 v27, v84
	v_mul_f32_e32 v30, v30, v30
	v_mul_f32_e32 v31, v31, v31
	s_nop 0
	v_fma_f32 v26, v26, v26, v30
	v_fma_f32 v27, v27, v27, v31
	s_waitcnt vmcnt(15)
	v_lshlrev_b32_e32 v30, 16, v96
	v_add_f32_e32 v58, v26, v27
	v_lshlrev_b32_e32 v26, 16, v100
	v_and_b32_e32 v27, 0xffff0000, v100
	v_and_b32_e32 v31, 0xffff0000, v96
	v_add_f32_e32 v74, v26, v30
	v_add_f32_e32 v75, v27, v31
	v_lshlrev_b32_e32 v26, 16, v101
	v_and_b32_e32 v27, 0xffff0000, v101
	v_lshlrev_b32_e32 v30, 16, v97
	v_and_b32_e32 v31, 0xffff0000, v97
	v_add_f32_e32 v76, v26, v30
	v_add_f32_e32 v77, v27, v31
	v_mov_b32_e32 v30, v75
	v_mov_b32_e32 v31, v77
	v_mov_b32_e32 v26, v74
	v_mov_b32_e32 v27, v76
	v_mul_f32_e32 v30, v30, v30
	v_mul_f32_e32 v31, v31, v31
	s_nop 0
	v_fma_f32 v26, v26, v26, v30
	v_fma_f32 v27, v27, v27, v31
	s_waitcnt vmcnt(12)
	v_lshlrev_b32_e32 v30, 16, v66
	v_add_f32_e32 v59, v26, v27
	v_lshlrev_b32_e32 v26, 16, v92
	v_and_b32_e32 v27, 0xffff0000, v92
	v_and_b32_e32 v31, 0xffff0000, v66
	v_add_f32_e32 v64, v26, v30
	v_add_f32_e32 v65, v27, v31
	v_lshlrev_b32_e32 v26, 16, v93
	v_and_b32_e32 v27, 0xffff0000, v93
	v_lshlrev_b32_e32 v30, 16, v67
	v_and_b32_e32 v31, 0xffff0000, v67
	v_add_f32_e32 v66, v26, v30
	v_add_f32_e32 v67, v27, v31
	v_mov_b32_e32 v30, v65
	v_mov_b32_e32 v31, v67
	v_mov_b32_e32 v26, v64
	v_mov_b32_e32 v27, v66
	v_mul_f32_e32 v30, v30, v30
	v_mul_f32_e32 v31, v31, v31
	s_nop 0
	v_fma_f32 v26, v26, v26, v30
	v_fma_f32 v27, v27, v27, v31
	s_waitcnt vmcnt(9)
	v_lshlrev_b32_e32 v30, 16, v60
	v_add_f32_e32 v92, v26, v27
	v_lshlrev_b32_e32 v26, 16, v54
	v_and_b32_e32 v27, 0xffff0000, v54
	v_and_b32_e32 v31, 0xffff0000, v60
	v_add_f32_e32 v56, v26, v30
	v_add_f32_e32 v57, v27, v31
	v_lshlrev_b32_e32 v26, 16, v55
	v_and_b32_e32 v27, 0xffff0000, v55
	v_lshlrev_b32_e32 v30, 16, v61
	v_and_b32_e32 v31, 0xffff0000, v61
	v_add_f32_e32 v54, v26, v30
	v_add_f32_e32 v55, v27, v31
	v_mov_b32_e32 v30, v57
	v_mov_b32_e32 v31, v55
	v_mov_b32_e32 v26, v56
	v_mov_b32_e32 v27, v54
	v_mul_f32_e32 v30, v30, v30
	v_mul_f32_e32 v31, v31, v31
	v_lshl_add_u64 v[60:61], v[6:7], 0, v[0:1]
	v_fma_f32 v26, v26, v26, v30
	v_fma_f32 v27, v27, v27, v31
	v_lshl_add_u64 v[6:7], v[8:9], 0, s[48:49]
	v_add_f32_e32 v30, v26, v27
	v_add_f32_dpp v26, v34, v34 quad_perm:[1,0,3,2] row_mask:0xf bank_mask:0xf bound_ctrl:1
	v_lshl_add_u64 v[148:149], v[6:7], 0, v[0:1]
	s_nop 0
	v_add_f32_dpp v26, v26, v26 quad_perm:[2,3,0,1] row_mask:0xf bank_mask:0xf bound_ctrl:1
	s_nop 1
	v_add_f32_dpp v26, v26, v26 row_half_mirror row_mask:0xf bank_mask:0xf bound_ctrl:1
	s_nop 1
	v_add_f32_dpp v26, v26, v26 row_mirror row_mask:0xf bank_mask:0xf bound_ctrl:1
	s_nop 0
	v_readlane_b32 s12, v26, 16
	v_readlane_b32 s13, v26, 48
	v_readlane_b32 s8, v26, 0
	v_readlane_b32 s9, v26, 32
	v_mov_b32_e32 v26, s12
	v_mov_b32_e32 v27, s13
	v_add_f32_e32 v26, s8, v26
	v_add_f32_e32 v27, s9, v27
	s_nop 0
	v_add_f32_e32 v26, v26, v27
	v_fmamk_f32 v26, v26, 0x3b800000, v252
	v_cmp_gt_f32_e64 s[36:37], s55, v26
	v_mul_f32_e32 v27, 0x4f800000, v26
	s_nop 0
	v_cndmask_b32_e64 v215, v26, v27, s[36:37]
	v_add_f32_dpp v26, v35, v35 quad_perm:[1,0,3,2] row_mask:0xf bank_mask:0xf bound_ctrl:1
	v_sqrt_f32_e32 v218, v215
	s_nop 0
	v_add_f32_dpp v26, v26, v26 quad_perm:[2,3,0,1] row_mask:0xf bank_mask:0xf bound_ctrl:1
	v_add_u32_e32 v219, -1, v218
	s_nop 0
	v_add_f32_dpp v26, v26, v26 row_half_mirror row_mask:0xf bank_mask:0xf bound_ctrl:1
	v_add_u32_e32 v217, 1, v218
	s_nop 0
	v_add_f32_dpp v26, v26, v26 row_mirror row_mask:0xf bank_mask:0xf bound_ctrl:1
	s_nop 0
	v_readlane_b32 s12, v26, 16
	v_readlane_b32 s13, v26, 48
	v_readlane_b32 s8, v26, 0
	v_readlane_b32 s9, v26, 32
	v_mov_b32_e32 v26, s12
	v_mov_b32_e32 v27, s13
	v_add_f32_e32 v26, s8, v26
	v_add_f32_e32 v27, s9, v27
	s_nop 0
	v_add_f32_e32 v26, v26, v27
	v_fmamk_f32 v26, v26, 0x3b800000, v252
	v_cmp_gt_f32_e64 s[34:35], s55, v26
	v_mul_f32_e32 v27, 0x4f800000, v26
	s_nop 0
	v_cndmask_b32_e64 v206, v26, v27, s[34:35]
	v_add_f32_dpp v26, v38, v38 quad_perm:[1,0,3,2] row_mask:0xf bank_mask:0xf bound_ctrl:1
	v_sqrt_f32_e32 v208, v206
	s_nop 0
	v_add_f32_dpp v26, v26, v26 quad_perm:[2,3,0,1] row_mask:0xf bank_mask:0xf bound_ctrl:1
	v_add_u32_e32 v212, -1, v208
	s_nop 0
	v_add_f32_dpp v26, v26, v26 row_half_mirror row_mask:0xf bank_mask:0xf bound_ctrl:1
	v_add_u32_e32 v210, 1, v208
	s_nop 0
	v_add_f32_dpp v26, v26, v26 row_mirror row_mask:0xf bank_mask:0xf bound_ctrl:1
	s_nop 0
	v_readlane_b32 s12, v26, 16
	v_readlane_b32 s13, v26, 48
	v_readlane_b32 s8, v26, 0
	v_readlane_b32 s9, v26, 32
	v_mov_b32_e32 v26, s12
	v_mov_b32_e32 v27, s13
	v_add_f32_e32 v26, s8, v26
	v_add_f32_e32 v27, s9, v27
	s_nop 0
	v_add_f32_e32 v26, v26, v27
	v_fmamk_f32 v26, v26, 0x3b800000, v252
	v_cmp_gt_f32_e64 s[28:29], s55, v26
	v_mul_f32_e32 v27, 0x4f800000, v26
	s_nop 0
	v_cndmask_b32_e64 v200, v26, v27, s[28:29]
	v_add_f32_dpp v26, v39, v39 quad_perm:[1,0,3,2] row_mask:0xf bank_mask:0xf bound_ctrl:1
	v_sqrt_f32_e32 v203, v200
	s_nop 0
	v_add_f32_dpp v26, v26, v26 quad_perm:[2,3,0,1] row_mask:0xf bank_mask:0xf bound_ctrl:1
	v_add_u32_e32 v204, -1, v203
	s_nop 0
	v_add_f32_dpp v26, v26, v26 row_half_mirror row_mask:0xf bank_mask:0xf bound_ctrl:1
	v_add_u32_e32 v201, 1, v203
	s_nop 0
	v_add_f32_dpp v26, v26, v26 row_mirror row_mask:0xf bank_mask:0xf bound_ctrl:1
	s_nop 0
	v_readlane_b32 s12, v26, 16
	v_readlane_b32 s13, v26, 48
	v_readlane_b32 s8, v26, 0
	v_readlane_b32 s9, v26, 32
	v_mov_b32_e32 v26, s12
	v_mov_b32_e32 v27, s13
	v_add_f32_e32 v26, s8, v26
	v_add_f32_e32 v27, s9, v27
	s_nop 0
	v_add_f32_e32 v26, v26, v27
	v_fmamk_f32 v26, v26, 0x3b800000, v252
	v_cmp_gt_f32_e64 s[24:25], s55, v26
	v_mul_f32_e32 v27, 0x4f800000, v26
	s_nop 0
	v_cndmask_b32_e64 v190, v26, v27, s[24:25]
	v_add_f32_dpp v26, v58, v58 quad_perm:[1,0,3,2] row_mask:0xf bank_mask:0xf bound_ctrl:1
	v_sqrt_f32_e32 v192, v190
	s_nop 0
	v_add_f32_dpp v26, v26, v26 quad_perm:[2,3,0,1] row_mask:0xf bank_mask:0xf bound_ctrl:1
	v_add_u32_e32 v198, -1, v192
	s_nop 0
	v_add_f32_dpp v26, v26, v26 row_half_mirror row_mask:0xf bank_mask:0xf bound_ctrl:1
	v_add_u32_e32 v195, 1, v192
	s_nop 0
	v_add_f32_dpp v26, v26, v26 row_mirror row_mask:0xf bank_mask:0xf bound_ctrl:1
	s_nop 0
	v_readlane_b32 s12, v26, 16
	v_readlane_b32 s13, v26, 48
	v_readlane_b32 s8, v26, 0
	v_readlane_b32 s9, v26, 32
	v_mov_b32_e32 v26, s12
	v_mov_b32_e32 v27, s13
	v_add_f32_e32 v26, s8, v26
	v_add_f32_e32 v27, s9, v27
	s_nop 0
	v_add_f32_e32 v26, v26, v27
	v_fmamk_f32 v26, v26, 0x3b800000, v252
	v_cmp_gt_f32_e64 s[20:21], s55, v26
	v_mul_f32_e32 v27, 0x4f800000, v26
	s_nop 0
	v_cndmask_b32_e64 v184, v26, v27, s[20:21]
	v_add_f32_dpp v26, v59, v59 quad_perm:[1,0,3,2] row_mask:0xf bank_mask:0xf bound_ctrl:1
	v_sqrt_f32_e32 v187, v184
	s_nop 0
	v_add_f32_dpp v26, v26, v26 quad_perm:[2,3,0,1] row_mask:0xf bank_mask:0xf bound_ctrl:1
	v_add_u32_e32 v188, -1, v187
	s_nop 0
	v_add_f32_dpp v26, v26, v26 row_half_mirror row_mask:0xf bank_mask:0xf bound_ctrl:1
	v_add_u32_e32 v185, 1, v187
	s_nop 0
	v_add_f32_dpp v26, v26, v26 row_mirror row_mask:0xf bank_mask:0xf bound_ctrl:1
	s_nop 0
	v_readlane_b32 s12, v26, 16
	v_readlane_b32 s13, v26, 48
	v_readlane_b32 s8, v26, 0
	v_readlane_b32 s9, v26, 32
	v_mov_b32_e32 v26, s12
	v_mov_b32_e32 v27, s13
	v_add_f32_e32 v26, s8, v26
	v_add_f32_e32 v27, s9, v27
	s_nop 0
	v_add_f32_e32 v26, v26, v27
	v_fmamk_f32 v26, v26, 0x3b800000, v252
	v_cmp_gt_f32_e64 s[16:17], s55, v26
	v_mul_f32_e32 v27, 0x4f800000, v26
	s_nop 0
	v_cndmask_b32_e64 v168, v26, v27, s[16:17]
	v_add_f32_dpp v26, v92, v92 quad_perm:[1,0,3,2] row_mask:0xf bank_mask:0xf bound_ctrl:1
	v_sqrt_f32_e32 v170, v168
	s_nop 0
	v_add_f32_dpp v26, v26, v26 quad_perm:[2,3,0,1] row_mask:0xf bank_mask:0xf bound_ctrl:1
	v_add_u32_e32 v176, -1, v170
	s_nop 0
	v_add_f32_dpp v26, v26, v26 row_half_mirror row_mask:0xf bank_mask:0xf bound_ctrl:1
	v_add_u32_e32 v173, 1, v170
	s_nop 0
	v_add_f32_dpp v26, v26, v26 row_mirror row_mask:0xf bank_mask:0xf bound_ctrl:1
	s_nop 0
	v_readlane_b32 s12, v26, 16
	v_readlane_b32 s13, v26, 48
	v_readlane_b32 s8, v26, 0
	v_readlane_b32 s9, v26, 32
	v_mov_b32_e32 v26, s12
	v_mov_b32_e32 v27, s13
	v_add_f32_e32 v26, s8, v26
	v_add_f32_e32 v27, s9, v27
	s_nop 0
	v_add_f32_e32 v26, v26, v27
	v_fmamk_f32 v26, v26, 0x3b800000, v252
	v_cmp_gt_f32_e64 s[12:13], s55, v26
	v_mul_f32_e32 v27, 0x4f800000, v26
	s_nop 0
	v_cndmask_b32_e64 v162, v26, v27, s[12:13]
	v_add_f32_dpp v26, v30, v30 quad_perm:[1,0,3,2] row_mask:0xf bank_mask:0xf bound_ctrl:1
	v_sqrt_f32_e32 v165, v162
	s_nop 0
	v_add_f32_dpp v26, v26, v26 quad_perm:[2,3,0,1] row_mask:0xf bank_mask:0xf bound_ctrl:1
	v_add_u32_e32 v166, -1, v165
	s_nop 0
	v_add_f32_dpp v26, v26, v26 row_half_mirror row_mask:0xf bank_mask:0xf bound_ctrl:1
	v_add_u32_e32 v163, 1, v165
	s_nop 0
	v_add_f32_dpp v26, v26, v26 row_mirror row_mask:0xf bank_mask:0xf bound_ctrl:1
	s_nop 0
	v_readlane_b32 s33, v26, 16
	v_readlane_b32 s44, v26, 48
	v_readlane_b32 s8, v26, 0
	v_readlane_b32 s9, v26, 32
	v_mov_b32_e32 v26, s33
	v_mov_b32_e32 v27, s44
	v_add_f32_e32 v26, s8, v26
	v_add_f32_e32 v27, s9, v27
	s_nop 0
	v_add_f32_e32 v26, v26, v27
	v_fmamk_f32 v26, v26, 0x3b800000, v252
	v_cmp_gt_f32_e64 s[8:9], s55, v26
	v_mul_f32_e32 v27, 0x4f800000, v26
	s_nop 0
	v_cndmask_b32_e64 v152, v26, v27, s[8:9]
	global_load_dwordx2 v[146:147], v[4:5], off nt
	global_load_dwordx2 v[144:145], v[60:61], off nt
	global_load_dwordx2 v[58:59], v[148:149], off nt
	global_load_dwordx2 v[132:133], v[4:5], off offset:512 nt
	global_load_dwordx2 v[128:129], v[60:61], off offset:512 nt
	global_load_dwordx2 v[38:39], v[148:149], off offset:512 nt
	global_load_dwordx2 v[124:125], v[4:5], off offset:1024 nt
	global_load_dwordx2 v[120:121], v[60:61], off offset:1024 nt
	global_load_dwordx2 v[34:35], v[148:149], off offset:1024 nt
	global_load_dwordx2 v[116:117], v[4:5], off offset:1536 nt
	global_load_dwordx2 v[112:113], v[60:61], off offset:1536 nt
	global_load_dwordx2 v[30:31], v[148:149], off offset:1536 nt
	global_load_dwordx2 v[110:111], v[4:5], off offset:2048 nt
	global_load_dwordx2 v[108:109], v[60:61], off offset:2048 nt
	global_load_dwordx2 v[26:27], v[148:149], off offset:2048 nt
	global_load_dwordx2 v[104:105], v[4:5], off offset:2560 nt
	global_load_dwordx2 v[100:101], v[60:61], off offset:2560 nt
	global_load_dwordx2 v[8:9], v[148:149], off offset:2560 nt
	global_load_dwordx2 v[98:99], v[4:5], off offset:3072 nt
	global_load_dwordx2 v[96:97], v[60:61], off offset:3072 nt
	global_load_dwordx2 v[6:7], v[148:149], off offset:3072 nt
	global_load_dwordx2 v[92:93], v[4:5], off offset:3584 nt
	s_nop 0
	global_load_dwordx2 v[60:61], v[60:61], off offset:3584 nt
	s_nop 0
	global_load_dwordx2 v[4:5], v[148:149], off offset:3584 nt
	v_lshl_add_u64 v[148:149], v[2:3], 0, s[40:41]
	v_cmp_ge_f32_e64 s[40:41], 0, v178
	v_lshl_add_u64 v[148:149], v[148:149], 0, v[0:1]
	v_sqrt_f32_e32 v154, v152
	v_cndmask_b32_e64 v178, v214, v216, s[40:41]
	v_cmp_lt_f32_e64 s[40:41], 0, v179
	v_add_u32_e32 v160, -1, v154
	s_nop 0
	v_cndmask_b32_e64 v178, v178, v213, s[40:41]
	v_mul_f32_e32 v179, 0x37800000, v178
	v_cndmask_b32_e32 v178, v178, v179, vcc
	v_cmp_class_f32_e32 vcc, v211, v253
	v_add_u32_e32 v157, 1, v154
	s_nop 0
	v_cndmask_b32_e32 v178, v178, v211, vcc
	v_div_scale_f32 v179, s[40:41], v178, v178, 1.0
	v_rcp_f32_e32 v180, v179
	s_nop 0
	v_fma_f32 v181, -v179, v180, 1.0
	v_fmac_f32_e32 v180, v181, v180
	v_div_scale_f32 v181, vcc, 1.0, v178, 1.0
	v_mul_f32_e32 v211, v181, v180
	v_fma_f32 v213, -v179, v211, v181
	v_fmac_f32_e32 v211, v213, v180
	v_fma_f32 v179, -v179, v211, v181
	v_div_fmas_f32 v179, v179, v180, v211
	v_div_fixup_f32 v178, v179, v178, 1.0
	v_lshlrev_b32_e32 v180, 16, v24
	v_and_b32_e32 v181, 0xffff0000, v24
	v_lshlrev_b32_e32 v24, 16, v25
	v_and_b32_e32 v25, 0xffff0000, v25
	v_mul_f32_e32 v140, v140, v178
	v_mul_f32_e32 v141, v141, v178
	v_mul_f32_e32 v142, v142, v178
	v_mul_f32_e32 v143, v143, v178
	v_mul_f32_e32 v140, v140, v180
	v_mul_f32_e32 v141, v141, v181
	v_mul_f32_e32 v24, v142, v24
	v_mul_f32_e32 v25, v143, v25
	v_cvt_pk_bf16_f32 v140, v140, v141
	v_cvt_pk_bf16_f32 v141, v24, v25
	v_fma_f32 v24, -v209, v205, v202
	v_cmp_ge_f32_e32 vcc, 0, v24
	v_fma_f32 v25, -v207, v205, v202
	global_store_dwordx2 v[148:149], v[140:141], off
	v_cndmask_b32_e32 v24, v205, v209, vcc
	v_cmp_lt_f32_e32 vcc, 0, v25
	s_nop 1
	v_cndmask_b32_e32 v24, v24, v207, vcc
	v_mul_f32_e32 v25, 0x37800000, v24
	v_cndmask_b32_e64 v24, v24, v25, s[30:31]
	v_cmp_class_f32_e32 vcc, v202, v253
	s_nop 1
	v_cndmask_b32_e32 v24, v24, v202, vcc
	v_div_scale_f32 v25, s[30:31], v24, v24, 1.0
	v_rcp_f32_e32 v140, v25
	s_nop 0
	v_fma_f32 v141, -v25, v140, 1.0
	v_fmac_f32_e32 v140, v141, v140
	v_div_scale_f32 v141, vcc, 1.0, v24, 1.0
	v_mul_f32_e32 v142, v141, v140
	v_fma_f32 v143, -v25, v142, v141
	v_fmac_f32_e32 v142, v143, v140
	v_fma_f32 v25, -v25, v142, v141
	v_div_fmas_f32 v25, v25, v140, v142
	v_div_fixup_f32 v24, v25, v24, 1.0
	v_lshlrev_b32_e32 v140, 16, v22
	v_and_b32_e32 v141, 0xffff0000, v22
	v_lshlrev_b32_e32 v22, 16, v23
	v_and_b32_e32 v23, 0xffff0000, v23
	v_mul_f32_e32 v134, v134, v24
	v_mul_f32_e32 v135, v135, v24
	v_mul_f32_e32 v25, v137, v24
	v_mul_f32_e32 v24, v136, v24
	s_nop 0
	v_mul_f32_e32 v22, v24, v22
	v_mul_f32_e32 v23, v25, v23
	v_mul_f32_e32 v24, v134, v140
	v_mul_f32_e32 v25, v135, v141
	s_nop 0
	v_cvt_pk_bf16_f32 v24, v24, v25
	v_cvt_pk_bf16_f32 v25, v22, v23
	v_fma_f32 v22, -v199, v197, v194
	v_cmp_ge_f32_e32 vcc, 0, v22
	v_fma_f32 v23, -v196, v197, v194
	global_store_dwordx2 v[148:149], v[24:25], off offset:512
	v_cndmask_b32_e32 v22, v197, v199, vcc
	v_cmp_lt_f32_e32 vcc, 0, v23
	s_nop 1
	v_cndmask_b32_e32 v22, v22, v196, vcc
	v_mul_f32_e32 v23, 0x37800000, v22
	v_cndmask_b32_e64 v22, v22, v23, s[26:27]
	v_cmp_class_f32_e32 vcc, v194, v253
	s_nop 1
	v_cndmask_b32_e32 v22, v22, v194, vcc
	v_div_scale_f32 v23, s[26:27], v22, v22, 1.0
	v_rcp_f32_e32 v24, v23
	s_nop 0
	v_fma_f32 v25, -v23, v24, 1.0
	v_fmac_f32_e32 v24, v25, v24
	v_div_scale_f32 v25, vcc, 1.0, v22, 1.0
	v_mul_f32_e32 v134, v25, v24
	v_fma_f32 v135, -v23, v134, v25
	v_fmac_f32_e32 v134, v135, v24
	v_fma_f32 v23, -v23, v134, v25
	v_div_fmas_f32 v23, v23, v24, v134
	v_div_fixup_f32 v22, v23, v22, 1.0
	v_lshlrev_b32_e32 v24, 16, v20
	v_and_b32_e32 v25, 0xffff0000, v20
	v_lshlrev_b32_e32 v20, 16, v21
	v_and_b32_e32 v21, 0xffff0000, v21
	v_mul_f32_e32 v130, v130, v22
	v_mul_f32_e32 v131, v131, v22
	v_mul_f32_e32 v23, v123, v22
	v_mul_f32_e32 v22, v122, v22
	s_nop 0
	v_mul_f32_e32 v20, v22, v20
	v_mul_f32_e32 v21, v23, v21
	v_mul_f32_e32 v22, v130, v24
	v_mul_f32_e32 v23, v131, v25
	s_nop 0
	v_cvt_pk_bf16_f32 v22, v22, v23
	v_cvt_pk_bf16_f32 v23, v20, v21
	v_fma_f32 v20, -v193, v189, v186
	v_cmp_ge_f32_e32 vcc, 0, v20
	v_fma_f32 v21, -v191, v189, v186
	global_store_dwordx2 v[148:149], v[22:23], off offset:1024
	v_cndmask_b32_e32 v20, v189, v193, vcc
	v_cmp_lt_f32_e32 vcc, 0, v21
	s_nop 1
	v_cndmask_b32_e32 v20, v20, v191, vcc
	v_mul_f32_e32 v21, 0x37800000, v20
	v_cndmask_b32_e64 v20, v20, v21, s[22:23]
	v_cmp_class_f32_e32 vcc, v186, v253
	s_nop 1
	v_cndmask_b32_e32 v20, v20, v186, vcc
	v_div_scale_f32 v21, s[22:23], v20, v20, 1.0
	v_rcp_f32_e32 v22, v21
	s_nop 0
	v_fma_f32 v23, -v21, v22, 1.0
	v_fmac_f32_e32 v22, v23, v22
	v_div_scale_f32 v23, vcc, 1.0, v20, 1.0
	v_mul_f32_e32 v24, v23, v22
	v_fma_f32 v25, -v21, v24, v23
	v_fmac_f32_e32 v24, v25, v22
	v_fma_f32 v21, -v21, v24, v23
	v_div_fmas_f32 v21, v21, v22, v24
	v_div_fixup_f32 v20, v21, v20, 1.0
	v_lshlrev_b32_e32 v22, 16, v18
	v_and_b32_e32 v23, 0xffff0000, v18
	v_lshlrev_b32_e32 v18, 16, v19
	v_and_b32_e32 v19, 0xffff0000, v19
	v_mul_f32_e32 v24, v86, v20
	v_mul_f32_e32 v25, v87, v20
	v_mul_f32_e32 v21, v89, v20
	v_mul_f32_e32 v20, v88, v20
	s_nop 0
	v_mul_f32_e32 v18, v20, v18
	v_mul_f32_e32 v19, v21, v19
	v_mul_f32_e32 v20, v24, v22
	v_mul_f32_e32 v21, v25, v23
	s_nop 0
	v_cvt_pk_bf16_f32 v20, v20, v21
	v_cvt_pk_bf16_f32 v21, v18, v19
	v_fma_f32 v18, -v177, v175, v172
	v_cmp_ge_f32_e32 vcc, 0, v18
	v_fma_f32 v19, -v174, v175, v172
	global_store_dwordx2 v[148:149], v[20:21], off offset:1536
	v_cndmask_b32_e32 v18, v175, v177, vcc
	v_cmp_lt_f32_e32 vcc, 0, v19
	s_nop 1
	v_cndmask_b32_e32 v18, v18, v174, vcc
	v_mul_f32_e32 v19, 0x37800000, v18
	v_cndmask_b32_e64 v18, v18, v19, s[18:19]
	v_cmp_class_f32_e32 vcc, v172, v253
	s_nop 1
	v_cndmask_b32_e32 v18, v18, v172, vcc
	v_div_scale_f32 v19, s[18:19], v18, v18, 1.0
	v_rcp_f32_e32 v20, v19
	s_nop 0
	v_fma_f32 v21, -v19, v20, 1.0
	v_fmac_f32_e32 v20, v21, v20
	v_div_scale_f32 v21, vcc, 1.0, v18, 1.0
	v_mul_f32_e32 v22, v21, v20
	v_fma_f32 v23, -v19, v22, v21
	v_fmac_f32_e32 v22, v23, v20
	v_fma_f32 v19, -v19, v22, v21
	v_div_fmas_f32 v19, v19, v20, v22
	v_div_fixup_f32 v18, v19, v18, 1.0
	v_lshlrev_b32_e32 v20, 16, v16
	v_and_b32_e32 v21, 0xffff0000, v16
	v_lshlrev_b32_e32 v16, 16, v17
	v_and_b32_e32 v17, 0xffff0000, v17
	v_mul_f32_e32 v22, v78, v18
	v_mul_f32_e32 v23, v79, v18
	v_mul_f32_e32 v19, v81, v18
	v_mul_f32_e32 v18, v80, v18
	s_nop 0
	v_mul_f32_e32 v16, v18, v16
	v_mul_f32_e32 v17, v19, v17
	v_mul_f32_e32 v18, v22, v20
	v_mul_f32_e32 v19, v23, v21
	s_nop 0
	v_cvt_pk_bf16_f32 v18, v18, v19
	v_cvt_pk_bf16_f32 v19, v16, v17
	v_fma_f32 v16, -v171, v167, v164
	v_cmp_ge_f32_e32 vcc, 0, v16
	v_fma_f32 v17, -v169, v167, v164
	global_store_dwordx2 v[148:149], v[18:19], off offset:2048
	v_cndmask_b32_e32 v16, v167, v171, vcc
	v_cmp_lt_f32_e32 vcc, 0, v17
	s_nop 1
	v_cndmask_b32_e32 v16, v16, v169, vcc
	v_mul_f32_e32 v17, 0x37800000, v16
	v_cndmask_b32_e64 v16, v16, v17, s[14:15]
	v_cmp_class_f32_e32 vcc, v164, v253
	s_nop 1
	v_cndmask_b32_e32 v16, v16, v164, vcc
	v_div_scale_f32 v17, s[14:15], v16, v16, 1.0
	v_rcp_f32_e32 v18, v17
	s_nop 0
	v_fma_f32 v19, -v17, v18, 1.0
	v_fmac_f32_e32 v18, v19, v18
	v_div_scale_f32 v19, vcc, 1.0, v16, 1.0
	v_mul_f32_e32 v20, v19, v18
	v_fma_f32 v21, -v17, v20, v19
	v_fmac_f32_e32 v20, v21, v18
	v_fma_f32 v17, -v17, v20, v19
	v_div_fmas_f32 v17, v17, v18, v20
	v_div_fixup_f32 v16, v17, v16, 1.0
	v_lshlrev_b32_e32 v18, 16, v14
	v_and_b32_e32 v19, 0xffff0000, v14
	v_lshlrev_b32_e32 v14, 16, v15
	v_and_b32_e32 v15, 0xffff0000, v15
	v_mul_f32_e32 v20, v70, v16
	v_mul_f32_e32 v21, v71, v16
	v_mul_f32_e32 v17, v73, v16
	v_mul_f32_e32 v16, v72, v16
	s_nop 0
	v_mul_f32_e32 v14, v16, v14
	v_mul_f32_e32 v15, v17, v15
	v_mul_f32_e32 v16, v20, v18
	v_mul_f32_e32 v17, v21, v19
	s_nop 0
	v_cvt_pk_bf16_f32 v16, v16, v17
	v_cvt_pk_bf16_f32 v17, v14, v15
	v_fma_f32 v14, -v161, v159, v156
	v_cmp_ge_f32_e32 vcc, 0, v14
	v_fma_f32 v15, -v158, v159, v156
	global_store_dwordx2 v[148:149], v[16:17], off offset:2560
	v_cndmask_b32_e32 v14, v159, v161, vcc
	v_cmp_lt_f32_e32 vcc, 0, v15
	s_nop 1
	v_cndmask_b32_e32 v14, v14, v158, vcc
	v_mul_f32_e32 v15, 0x37800000, v14
	v_cndmask_b32_e64 v14, v14, v15, s[10:11]
	v_cmp_class_f32_e32 vcc, v156, v253
	s_nop 1
	v_cndmask_b32_e32 v14, v14, v156, vcc
	v_div_scale_f32 v15, s[10:11], v14, v14, 1.0
	v_rcp_f32_e32 v16, v15
	s_nop 0
	v_fma_f32 v17, -v15, v16, 1.0
	v_fmac_f32_e32 v16, v17, v16
	v_div_scale_f32 v17, vcc, 1.0, v14, 1.0
	v_mul_f32_e32 v18, v17, v16
	v_fma_f32 v19, -v15, v18, v17
	v_fmac_f32_e32 v18, v19, v16
	v_fma_f32 v15, -v15, v18, v17
	v_div_fmas_f32 v15, v15, v16, v18
	v_div_fixup_f32 v14, v15, v14, 1.0
	v_lshlrev_b32_e32 v16, 16, v12
	v_and_b32_e32 v17, 0xffff0000, v12
	v_lshlrev_b32_e32 v12, 16, v13
	v_and_b32_e32 v13, 0xffff0000, v13
	v_mul_f32_e32 v18, v62, v14
	v_mul_f32_e32 v19, v63, v14
	v_mul_f32_e32 v15, v69, v14
	v_mul_f32_e32 v14, v68, v14
	s_nop 0
	v_mul_f32_e32 v12, v14, v12
	v_mul_f32_e32 v13, v15, v13
	v_mul_f32_e32 v14, v18, v16
	v_mul_f32_e32 v15, v19, v17
	s_nop 0
	v_cvt_pk_bf16_f32 v14, v14, v15
	v_cvt_pk_bf16_f32 v15, v12, v13
	v_fma_f32 v12, -v155, v151, v150
	v_cmp_ge_f32_e32 vcc, 0, v12
	v_fma_f32 v13, -v153, v151, v150
	global_store_dwordx2 v[148:149], v[14:15], off offset:3072
	v_cndmask_b32_e32 v12, v151, v155, vcc
	v_cmp_lt_f32_e32 vcc, 0, v13
	s_nop 1
	v_cndmask_b32_e32 v12, v12, v153, vcc
	v_mul_f32_e32 v13, 0x37800000, v12
	v_cndmask_b32_e64 v12, v12, v13, s[6:7]
	v_cmp_class_f32_e32 vcc, v150, v253
	s_nop 1
	v_cndmask_b32_e32 v12, v12, v150, vcc
	v_div_scale_f32 v13, s[6:7], v12, v12, 1.0
	v_rcp_f32_e32 v14, v13
	s_nop 0
	v_fma_f32 v15, -v13, v14, 1.0
	v_fmac_f32_e32 v14, v15, v14
	v_div_scale_f32 v15, vcc, 1.0, v12, 1.0
	v_mul_f32_e32 v16, v15, v14
	v_fma_f32 v17, -v13, v16, v15
	v_fmac_f32_e32 v16, v17, v14
	v_fma_f32 v13, -v13, v16, v15
	v_div_fmas_f32 v13, v13, v14, v16
	v_div_fixup_f32 v12, v13, v12, 1.0
	v_lshlrev_b32_e32 v14, 16, v10
	v_and_b32_e32 v15, 0xffff0000, v10
	v_lshlrev_b32_e32 v10, 16, v11
	v_and_b32_e32 v11, 0xffff0000, v11
	v_mul_f32_e32 v16, v44, v12
	v_mul_f32_e32 v17, v45, v12
	v_mul_f32_e32 v13, v51, v12
	v_mul_f32_e32 v12, v50, v12
	s_nop 0
	v_mul_f32_e32 v10, v12, v10
	v_mul_f32_e32 v11, v13, v11
	v_mul_f32_e32 v12, v16, v14
	v_mul_f32_e32 v13, v17, v15
	s_nop 0
	v_cvt_pk_bf16_f32 v12, v12, v13
	v_cvt_pk_bf16_f32 v13, v10, v11
	global_store_dwordx2 v[148:149], v[12:13], off offset:3584
	v_fma_f32 v12, -v219, v218, v215
	v_cmp_ge_f32_e32 vcc, 0, v12
	v_fma_f32 v13, -v217, v218, v215
	v_lshl_add_u64 v[10:11], v[2:3], 0, s[78:79]
	v_cndmask_b32_e32 v12, v218, v219, vcc
	v_cmp_lt_f32_e32 vcc, 0, v13
	v_lshl_add_u64 v[10:11], v[10:11], 0, v[0:1]
	s_nop 0
	v_cndmask_b32_e32 v12, v12, v217, vcc
	v_mul_f32_e32 v13, 0x37800000, v12
	v_cndmask_b32_e64 v12, v12, v13, s[36:37]
	v_cmp_class_f32_e32 vcc, v215, v253
	s_nop 1
	v_cndmask_b32_e32 v12, v12, v215, vcc
	v_div_scale_f32 v13, s[6:7], v12, v12, 1.0
	v_rcp_f32_e32 v14, v13
	s_nop 0
	v_fma_f32 v15, -v13, v14, 1.0
	v_fmac_f32_e32 v14, v15, v14
	v_div_scale_f32 v15, vcc, 1.0, v12, 1.0
	v_mul_f32_e32 v16, v15, v14
	v_fma_f32 v17, -v13, v16, v15
	v_fmac_f32_e32 v16, v17, v14
	v_fma_f32 v13, -v13, v16, v15
	v_div_fmas_f32 v13, v13, v14, v16
	v_div_fixup_f32 v12, v13, v12, 1.0
	v_lshlrev_b32_e32 v14, 16, v52
	v_and_b32_e32 v15, 0xffff0000, v52
	v_lshlrev_b32_e32 v16, 16, v53
	v_and_b32_e32 v17, 0xffff0000, v53
	v_mul_f32_e32 v18, v126, v12
	v_mul_f32_e32 v19, v127, v12
	v_mul_f32_e32 v13, v139, v12
	v_mul_f32_e32 v12, v138, v12
	v_mul_f32_e32 v14, v18, v14
	v_mul_f32_e32 v15, v19, v15
	v_mul_f32_e32 v12, v12, v16
	v_mul_f32_e32 v13, v13, v17
	v_cvt_pk_bf16_f32 v14, v14, v15
	v_cvt_pk_bf16_f32 v15, v12, v13
	v_fma_f32 v12, -v212, v208, v206
	v_cmp_ge_f32_e32 vcc, 0, v12
	v_fma_f32 v13, -v210, v208, v206
	global_store_dwordx2 v[10:11], v[14:15], off
	v_cndmask_b32_e32 v12, v208, v212, vcc
	v_cmp_lt_f32_e32 vcc, 0, v13
	s_nop 1
	v_cndmask_b32_e32 v12, v12, v210, vcc
	v_mul_f32_e32 v13, 0x37800000, v12
	v_cndmask_b32_e64 v12, v12, v13, s[34:35]
	v_cmp_class_f32_e32 vcc, v206, v253
	s_nop 1
	v_cndmask_b32_e32 v12, v12, v206, vcc
	v_div_scale_f32 v13, s[6:7], v12, v12, 1.0
	v_rcp_f32_e32 v14, v13
	s_nop 0
	v_fma_f32 v15, -v13, v14, 1.0
	v_fmac_f32_e32 v14, v15, v14
	v_div_scale_f32 v15, vcc, 1.0, v12, 1.0
	v_mul_f32_e32 v16, v15, v14
	v_fma_f32 v17, -v13, v16, v15
	v_fmac_f32_e32 v16, v17, v14
	v_fma_f32 v13, -v13, v16, v15
	v_div_fmas_f32 v13, v13, v14, v16
	v_div_fixup_f32 v12, v13, v12, 1.0
	v_lshlrev_b32_e32 v14, 16, v48
	v_and_b32_e32 v15, 0xffff0000, v48
	v_lshlrev_b32_e32 v16, 16, v49
	v_and_b32_e32 v17, 0xffff0000, v49
	v_mul_f32_e32 v18, v114, v12
	v_mul_f32_e32 v19, v115, v12
	v_mul_f32_e32 v13, v119, v12
	v_mul_f32_e32 v12, v118, v12
	v_mul_f32_e32 v14, v18, v14
	v_mul_f32_e32 v15, v19, v15
	v_mul_f32_e32 v12, v12, v16
	v_mul_f32_e32 v13, v13, v17
	v_cvt_pk_bf16_f32 v14, v14, v15
	v_cvt_pk_bf16_f32 v15, v12, v13
	v_fma_f32 v12, -v204, v203, v200
	v_cmp_ge_f32_e32 vcc, 0, v12
	v_fma_f32 v13, -v201, v203, v200
	global_store_dwordx2 v[10:11], v[14:15], off offset:512
	v_cndmask_b32_e32 v12, v203, v204, vcc
	v_cmp_lt_f32_e32 vcc, 0, v13
	s_nop 1
	v_cndmask_b32_e32 v12, v12, v201, vcc
	v_mul_f32_e32 v13, 0x37800000, v12
	v_cndmask_b32_e64 v12, v12, v13, s[28:29]
	v_cmp_class_f32_e32 vcc, v200, v253
	s_nop 1
	v_cndmask_b32_e32 v12, v12, v200, vcc
	v_div_scale_f32 v13, s[6:7], v12, v12, 1.0
	v_rcp_f32_e32 v14, v13
	s_nop 0
	v_fma_f32 v15, -v13, v14, 1.0
	v_fmac_f32_e32 v14, v15, v14
	v_div_scale_f32 v15, vcc, 1.0, v12, 1.0
	v_mul_f32_e32 v16, v15, v14
	v_fma_f32 v17, -v13, v16, v15
	v_fmac_f32_e32 v16, v17, v14
	v_fma_f32 v13, -v13, v16, v15
	v_div_fmas_f32 v13, v13, v14, v16
	v_div_fixup_f32 v12, v13, v12, 1.0
	v_lshlrev_b32_e32 v14, 16, v46
	v_and_b32_e32 v15, 0xffff0000, v46
	v_lshlrev_b32_e32 v16, 16, v47
	v_and_b32_e32 v17, 0xffff0000, v47
	v_mul_f32_e32 v18, v102, v12
	v_mul_f32_e32 v19, v103, v12
	v_mul_f32_e32 v13, v107, v12
	v_mul_f32_e32 v12, v106, v12
	v_mul_f32_e32 v14, v18, v14
	v_mul_f32_e32 v15, v19, v15
	v_mul_f32_e32 v12, v12, v16
	v_mul_f32_e32 v13, v13, v17
	v_cvt_pk_bf16_f32 v14, v14, v15
	v_cvt_pk_bf16_f32 v15, v12, v13
	v_fma_f32 v12, -v198, v192, v190
	v_cmp_ge_f32_e32 vcc, 0, v12
	v_fma_f32 v13, -v195, v192, v190
	global_store_dwordx2 v[10:11], v[14:15], off offset:1024
	v_cndmask_b32_e32 v12, v192, v198, vcc
	v_cmp_lt_f32_e32 vcc, 0, v13
	s_nop 1
	v_cndmask_b32_e32 v12, v12, v195, vcc
	v_mul_f32_e32 v13, 0x37800000, v12
	v_cndmask_b32_e64 v12, v12, v13, s[24:25]
	v_cmp_class_f32_e32 vcc, v190, v253
	s_nop 1
	v_cndmask_b32_e32 v12, v12, v190, vcc
	v_div_scale_f32 v13, s[6:7], v12, v12, 1.0
	v_rcp_f32_e32 v14, v13
	s_nop 0
	v_fma_f32 v15, -v13, v14, 1.0
	v_fmac_f32_e32 v14, v15, v14
	v_div_scale_f32 v15, vcc, 1.0, v12, 1.0
	v_mul_f32_e32 v16, v15, v14
	v_fma_f32 v17, -v13, v16, v15
	v_fmac_f32_e32 v16, v17, v14
	v_fma_f32 v13, -v13, v16, v15
	v_div_fmas_f32 v13, v13, v14, v16
	v_div_fixup_f32 v12, v13, v12, 1.0
	v_lshlrev_b32_e32 v14, 16, v42
	v_and_b32_e32 v15, 0xffff0000, v42
	v_lshlrev_b32_e32 v16, 16, v43
	v_and_b32_e32 v17, 0xffff0000, v43
	v_mul_f32_e32 v18, v90, v12
	v_mul_f32_e32 v19, v91, v12
	v_mul_f32_e32 v13, v95, v12
	v_mul_f32_e32 v12, v94, v12
	v_mul_f32_e32 v14, v18, v14
	v_mul_f32_e32 v15, v19, v15
	v_mul_f32_e32 v12, v12, v16
	v_mul_f32_e32 v13, v13, v17
	v_cvt_pk_bf16_f32 v14, v14, v15
	v_cvt_pk_bf16_f32 v15, v12, v13
	v_fma_f32 v12, -v188, v187, v184
	v_cmp_ge_f32_e32 vcc, 0, v12
	v_fma_f32 v13, -v185, v187, v184
	global_store_dwordx2 v[10:11], v[14:15], off offset:1536
	v_cndmask_b32_e32 v12, v187, v188, vcc
	v_cmp_lt_f32_e32 vcc, 0, v13
	s_nop 1
	v_cndmask_b32_e32 v12, v12, v185, vcc
	v_mul_f32_e32 v13, 0x37800000, v12
	v_cndmask_b32_e64 v12, v12, v13, s[20:21]
	v_cmp_class_f32_e32 vcc, v184, v253
	s_nop 1
	v_cndmask_b32_e32 v12, v12, v184, vcc
	v_div_scale_f32 v13, s[6:7], v12, v12, 1.0
	v_rcp_f32_e32 v14, v13
	s_nop 0
	v_fma_f32 v15, -v13, v14, 1.0
	v_fmac_f32_e32 v14, v15, v14
	v_div_scale_f32 v15, vcc, 1.0, v12, 1.0
	v_mul_f32_e32 v16, v15, v14
	v_fma_f32 v17, -v13, v16, v15
	v_fmac_f32_e32 v16, v17, v14
	v_fma_f32 v13, -v13, v16, v15
	v_div_fmas_f32 v13, v13, v14, v16
	v_div_fixup_f32 v12, v13, v12, 1.0
	v_lshlrev_b32_e32 v14, 16, v40
	v_and_b32_e32 v15, 0xffff0000, v40
	v_lshlrev_b32_e32 v16, 16, v41
	v_and_b32_e32 v17, 0xffff0000, v41
; #define GAS __attribute__((address_space(1)))
; #define LAS __attribute__((address_space(3)))
; template <bool HG>
; __device__ __forceinline__ void readout_phase2(const Args& a, Frame& F, const float* gain, int nrows) {
;     ...
;     RO_LOAD(f0, b0, g0, nw); RO_LOAD(f1, b1, g1, nw + 2048); RO_LOAD(f2, b2, g2, nw + 2 * 2048);
;     if (HG) { for (int q = F.tid; q < D / 4; q += NWAVES * 64) ((LAS f32x4*)GL)[q] = ((const GAS f32x4*)gain)[q];
;               asm volatile("s_waitcnt lgkmcnt(0)" ::: "memory"); __builtin_amdgcn_s_barrier(); asm volatile("" ::: "memory"); }
;     RO_FINISH(f0, b0, g0, nw);            RO_LOAD(f0, b0, g0, nw + 3 * 2048);
;     RO_FINISH(f1, b1, g1, nw + 2048);     RO_LOAD(f1, b1, g1, nw + 4 * 2048);
;     RO_FINISH(f2, b2, g2, nw + 2 * 2048); RO_LOAD(f2, b2, g2, nw + 5 * 2048);
;     RO_FINISH(f0, b0, g0, nw + 3 * 2048); RO_LOAD(f0, b0, g0, nw + 6 * 2048);
;     RO_FINISH(f1, b1, g1, nw + 4 * 2048); RO_LOAD(f1, b1, g1, nw + 7 * 2048);
;     RO_FINISH(f2, b2, g2, nw + 5 * 2048);
;     const bool cx = ML + nw < nrows;
;     RO_LOAD(f2, b2, g2, cx ? ML + nw : nw + 7 * 2048);
;     RO_FINISH(f0, b0, g0, nw + 6 * 2048);
;     RO_FINISH(f1, b1, g1, nw + 7 * 2048);
;     if (cx) RO_FINISH(f2, b2, g2, ML + nw);
	v_mul_f32_e32 v18, v82, v12
	v_mul_f32_e32 v19, v83, v12
	v_mul_f32_e32 v13, v85, v12
	v_mul_f32_e32 v12, v84, v12
	v_mul_f32_e32 v14, v18, v14
	v_mul_f32_e32 v15, v19, v15
	v_mul_f32_e32 v12, v12, v16
	v_mul_f32_e32 v13, v13, v17
	v_cvt_pk_bf16_f32 v14, v14, v15
	v_cvt_pk_bf16_f32 v15, v12, v13
	v_fma_f32 v12, -v176, v170, v168
	v_cmp_ge_f32_e32 vcc, 0, v12
	v_fma_f32 v13, -v173, v170, v168
	global_store_dwordx2 v[10:11], v[14:15], off offset:2048
	v_cndmask_b32_e32 v12, v170, v176, vcc
	v_cmp_lt_f32_e32 vcc, 0, v13
	s_nop 1
	v_cndmask_b32_e32 v12, v12, v173, vcc
	v_mul_f32_e32 v13, 0x37800000, v12
	v_cndmask_b32_e64 v12, v12, v13, s[16:17]
	v_cmp_class_f32_e32 vcc, v168, v253
	s_nop 1
	v_cndmask_b32_e32 v12, v12, v168, vcc
	v_div_scale_f32 v13, s[6:7], v12, v12, 1.0
	v_rcp_f32_e32 v14, v13
	s_nop 0
	v_fma_f32 v15, -v13, v14, 1.0
	v_fmac_f32_e32 v14, v15, v14
	v_div_scale_f32 v15, vcc, 1.0, v12, 1.0
	v_mul_f32_e32 v16, v15, v14
	v_fma_f32 v17, -v13, v16, v15
	v_fmac_f32_e32 v16, v17, v14
	v_fma_f32 v13, -v13, v16, v15
	v_div_fmas_f32 v13, v13, v14, v16
	v_div_fixup_f32 v12, v13, v12, 1.0
	v_lshlrev_b32_e32 v14, 16, v36
	v_and_b32_e32 v15, 0xffff0000, v36
	v_lshlrev_b32_e32 v16, 16, v37
	v_and_b32_e32 v17, 0xffff0000, v37
	v_mul_f32_e32 v18, v74, v12
	v_mul_f32_e32 v19, v75, v12
	v_mul_f32_e32 v13, v77, v12
	v_mul_f32_e32 v12, v76, v12
	v_mul_f32_e32 v14, v18, v14
	v_mul_f32_e32 v15, v19, v15
	v_mul_f32_e32 v12, v12, v16
	v_mul_f32_e32 v13, v13, v17
	v_cvt_pk_bf16_f32 v14, v14, v15
	v_cvt_pk_bf16_f32 v15, v12, v13
	v_fma_f32 v12, -v166, v165, v162
	v_cmp_ge_f32_e32 vcc, 0, v12
	v_fma_f32 v13, -v163, v165, v162
	global_store_dwordx2 v[10:11], v[14:15], off offset:2560
	v_cndmask_b32_e32 v12, v165, v166, vcc
	v_cmp_lt_f32_e32 vcc, 0, v13
	s_nop 1
	v_cndmask_b32_e32 v12, v12, v163, vcc
	v_mul_f32_e32 v13, 0x37800000, v12
	v_cndmask_b32_e64 v12, v12, v13, s[12:13]
	v_cmp_class_f32_e32 vcc, v162, v253
	s_nop 1
	v_cndmask_b32_e32 v12, v12, v162, vcc
	v_div_scale_f32 v13, s[6:7], v12, v12, 1.0
	v_rcp_f32_e32 v14, v13
	s_nop 0
	v_fma_f32 v15, -v13, v14, 1.0
	v_fmac_f32_e32 v14, v15, v14
	v_div_scale_f32 v15, vcc, 1.0, v12, 1.0
	v_mul_f32_e32 v16, v15, v14
	v_fma_f32 v17, -v13, v16, v15
	v_fmac_f32_e32 v16, v17, v14
	v_fma_f32 v13, -v13, v16, v15
	v_div_fmas_f32 v13, v13, v14, v16
	v_div_fixup_f32 v12, v13, v12, 1.0
	v_lshlrev_b32_e32 v14, 16, v32
	v_and_b32_e32 v15, 0xffff0000, v32
	v_lshlrev_b32_e32 v16, 16, v33
	v_and_b32_e32 v17, 0xffff0000, v33
	v_mul_f32_e32 v18, v64, v12
	v_mul_f32_e32 v19, v65, v12
	v_mul_f32_e32 v13, v67, v12
	v_mul_f32_e32 v12, v66, v12
	v_mul_f32_e32 v14, v18, v14
	v_mul_f32_e32 v15, v19, v15
	v_mul_f32_e32 v12, v12, v16
	v_mul_f32_e32 v13, v13, v17
	v_cvt_pk_bf16_f32 v14, v14, v15
	v_cvt_pk_bf16_f32 v15, v12, v13
	v_fma_f32 v12, -v160, v154, v152
	v_cmp_ge_f32_e32 vcc, 0, v12
	v_fma_f32 v13, -v157, v154, v152
	global_store_dwordx2 v[10:11], v[14:15], off offset:3072
	v_cndmask_b32_e32 v12, v154, v160, vcc
	v_cmp_lt_f32_e32 vcc, 0, v13
	s_nop 1
	v_cndmask_b32_e32 v12, v12, v157, vcc
	v_mul_f32_e32 v13, 0x37800000, v12
	v_cndmask_b32_e64 v12, v12, v13, s[8:9]
	v_cmp_class_f32_e32 vcc, v152, v253
	s_nop 1
	v_cndmask_b32_e32 v12, v12, v152, vcc
	v_div_scale_f32 v13, s[6:7], v12, v12, 1.0
	v_rcp_f32_e32 v14, v13
	s_nop 0
	v_fma_f32 v15, -v13, v14, 1.0
	v_fmac_f32_e32 v14, v15, v14
	v_div_scale_f32 v15, vcc, 1.0, v12, 1.0
	v_mul_f32_e32 v16, v15, v14
	v_fma_f32 v17, -v13, v16, v15
	v_fmac_f32_e32 v16, v17, v14
	v_fma_f32 v13, -v13, v16, v15
	v_div_fmas_f32 v13, v13, v14, v16
	v_div_fixup_f32 v12, v13, v12, 1.0
	s_waitcnt vmcnt(47)
	v_lshlrev_b32_e32 v14, 16, v28
	v_and_b32_e32 v15, 0xffff0000, v28
	v_lshlrev_b32_e32 v16, 16, v29
	v_and_b32_e32 v17, 0xffff0000, v29
	v_mul_f32_e32 v18, v56, v12
	v_mul_f32_e32 v19, v57, v12
	v_mul_f32_e32 v13, v55, v12
	v_mul_f32_e32 v12, v54, v12
	v_mul_f32_e32 v14, v18, v14
	v_mul_f32_e32 v15, v19, v15
	v_mul_f32_e32 v12, v12, v16
	v_mul_f32_e32 v13, v13, v17
	v_cvt_pk_bf16_f32 v14, v14, v15
	v_cvt_pk_bf16_f32 v15, v12, v13
	global_store_dwordx2 v[10:11], v[14:15], off offset:3584
	s_cbranch_scc1 .LBB0_864
	s_waitcnt vmcnt(39)
	v_lshlrev_b32_e32 v10, 16, v146
	v_and_b32_e32 v11, 0xffff0000, v146
	s_waitcnt vmcnt(38)
	v_lshlrev_b32_e32 v12, 16, v144
	v_and_b32_e32 v13, 0xffff0000, v144
	v_add_f32_e32 v46, v10, v12
	v_add_f32_e32 v47, v11, v13
	v_lshlrev_b32_e32 v10, 16, v147
	v_and_b32_e32 v11, 0xffff0000, v147
	v_lshlrev_b32_e32 v12, 16, v145
	v_and_b32_e32 v13, 0xffff0000, v145
	v_add_f32_e32 v48, v10, v12
	v_add_f32_e32 v49, v11, v13
	v_mov_b32_e32 v12, v47
	v_mov_b32_e32 v13, v49
	v_mov_b32_e32 v10, v46
	v_mov_b32_e32 v11, v48
	v_mul_f32_e32 v12, v12, v12
	v_mul_f32_e32 v13, v13, v13
	s_ashr_i32 s83, s82, 31
	v_fma_f32 v10, v10, v10, v12
	v_fma_f32 v11, v11, v11, v13
	s_waitcnt vmcnt(35)
	v_lshlrev_b32_e32 v12, 16, v128
	v_add_f32_e32 v62, v10, v11
	v_lshlrev_b32_e32 v10, 16, v132
	v_and_b32_e32 v11, 0xffff0000, v132
	v_and_b32_e32 v13, 0xffff0000, v128
	v_add_f32_e32 v42, v10, v12
	v_add_f32_e32 v43, v11, v13
	v_lshlrev_b32_e32 v10, 16, v133
	v_and_b32_e32 v11, 0xffff0000, v133
	v_lshlrev_b32_e32 v12, 16, v129
	v_and_b32_e32 v13, 0xffff0000, v129
	v_add_f32_e32 v44, v10, v12
	v_add_f32_e32 v45, v11, v13
	v_mov_b32_e32 v12, v43
	v_mov_b32_e32 v13, v45
	v_mov_b32_e32 v10, v42
	v_mov_b32_e32 v11, v44
	v_mul_f32_e32 v12, v12, v12
	v_mul_f32_e32 v13, v13, v13
	s_lshl_b64 s[6:7], s[82:83], 12
	v_fma_f32 v10, v10, v10, v12
	v_fma_f32 v11, v11, v11, v13
	s_waitcnt vmcnt(32)
	v_lshlrev_b32_e32 v12, 16, v120
	v_add_f32_e32 v63, v10, v11
	v_lshlrev_b32_e32 v10, 16, v124
	v_and_b32_e32 v11, 0xffff0000, v124
	v_and_b32_e32 v13, 0xffff0000, v120
	v_add_f32_e32 v36, v10, v12
	v_add_f32_e32 v37, v11, v13
	v_lshlrev_b32_e32 v10, 16, v125
	v_and_b32_e32 v11, 0xffff0000, v125
	v_lshlrev_b32_e32 v12, 16, v121
	v_and_b32_e32 v13, 0xffff0000, v121
	v_add_f32_e32 v40, v10, v12
	v_add_f32_e32 v41, v11, v13
	v_mov_b32_e32 v12, v37
	v_mov_b32_e32 v13, v41
	v_mov_b32_e32 v10, v36
	v_mov_b32_e32 v11, v40
	v_mul_f32_e32 v12, v12, v12
	v_mul_f32_e32 v13, v13, v13
	v_lshl_add_u64 v[2:3], v[2:3], 0, s[6:7]
	v_fma_f32 v10, v10, v10, v12
	v_fma_f32 v11, v11, v11, v13
	s_waitcnt vmcnt(29)
	v_lshlrev_b32_e32 v12, 16, v112
	v_add_f32_e32 v64, v10, v11
	v_lshlrev_b32_e32 v10, 16, v116
	v_and_b32_e32 v11, 0xffff0000, v116
	v_and_b32_e32 v13, 0xffff0000, v112
	v_add_f32_e32 v28, v10, v12
	v_add_f32_e32 v29, v11, v13
	v_lshlrev_b32_e32 v10, 16, v117
	v_and_b32_e32 v11, 0xffff0000, v117
	v_lshlrev_b32_e32 v12, 16, v113
	v_and_b32_e32 v13, 0xffff0000, v113
	v_add_f32_e32 v32, v10, v12
	v_add_f32_e32 v33, v11, v13
	v_mov_b32_e32 v12, v29
	v_mov_b32_e32 v13, v33
	v_mov_b32_e32 v10, v28
	v_mov_b32_e32 v11, v32
	v_mul_f32_e32 v12, v12, v12
	v_mul_f32_e32 v13, v13, v13
	s_waitcnt vmcnt(17)
	v_lshlrev_b32_e32 v54, 16, v61
	v_fma_f32 v10, v10, v10, v12
	v_fma_f32 v11, v11, v11, v13
	v_lshlrev_b32_e32 v12, 16, v108
	v_add_f32_e32 v65, v10, v11
	v_lshlrev_b32_e32 v10, 16, v110
	v_and_b32_e32 v11, 0xffff0000, v110
	v_and_b32_e32 v13, 0xffff0000, v108
	v_add_f32_e32 v22, v10, v12
	v_add_f32_e32 v23, v11, v13
	v_lshlrev_b32_e32 v10, 16, v111
	v_and_b32_e32 v11, 0xffff0000, v111
	v_lshlrev_b32_e32 v12, 16, v109
	v_and_b32_e32 v13, 0xffff0000, v109
	v_add_f32_e32 v24, v10, v12
	v_add_f32_e32 v25, v11, v13
	v_mov_b32_e32 v12, v23
	v_mov_b32_e32 v13, v25
	v_mov_b32_e32 v10, v22
	v_mov_b32_e32 v11, v24
	v_mul_f32_e32 v12, v12, v12
	v_mul_f32_e32 v13, v13, v13
	v_and_b32_e32 v55, 0xffff0000, v61
	v_fma_f32 v10, v10, v10, v12
	v_fma_f32 v11, v11, v11, v13
	v_lshlrev_b32_e32 v12, 16, v100
	v_add_f32_e32 v53, v10, v11
	v_lshlrev_b32_e32 v10, 16, v104
	v_and_b32_e32 v11, 0xffff0000, v104
	v_and_b32_e32 v13, 0xffff0000, v100
	v_add_f32_e32 v18, v10, v12
	v_add_f32_e32 v19, v11, v13
	v_lshlrev_b32_e32 v10, 16, v105
	v_and_b32_e32 v11, 0xffff0000, v105
	v_lshlrev_b32_e32 v12, 16, v101
	v_and_b32_e32 v13, 0xffff0000, v101
	v_add_f32_e32 v20, v10, v12
	v_add_f32_e32 v21, v11, v13
	v_mov_b32_e32 v12, v19
	v_mov_b32_e32 v13, v21
	v_mov_b32_e32 v10, v18
	v_mov_b32_e32 v11, v20
	v_mul_f32_e32 v12, v12, v12
	v_mul_f32_e32 v13, v13, v13
	v_lshl_add_u64 v[2:3], v[2:3], 0, v[0:1]
	v_fma_f32 v10, v10, v10, v12
	v_fma_f32 v11, v11, v11, v13
	v_lshlrev_b32_e32 v12, 16, v96
	v_add_f32_e32 v52, v10, v11
	v_lshlrev_b32_e32 v10, 16, v98
	v_and_b32_e32 v11, 0xffff0000, v98
	v_and_b32_e32 v13, 0xffff0000, v96
	v_add_f32_e32 v14, v10, v12
	v_add_f32_e32 v15, v11, v13
	v_lshlrev_b32_e32 v10, 16, v99
	v_and_b32_e32 v11, 0xffff0000, v99
	v_lshlrev_b32_e32 v12, 16, v97
	v_and_b32_e32 v13, 0xffff0000, v97
	v_add_f32_e32 v16, v10, v12
	v_add_f32_e32 v17, v11, v13
	v_mov_b32_e32 v12, v15
	v_mov_b32_e32 v13, v17
	v_mov_b32_e32 v10, v14
	v_mov_b32_e32 v11, v16
	v_mul_f32_e32 v12, v12, v12
	v_mul_f32_e32 v13, v13, v13
	v_add_f32_dpp v0, v62, v62 quad_perm:[1,0,3,2] row_mask:0xf bank_mask:0xf bound_ctrl:1
	v_fma_f32 v10, v10, v10, v12
	v_fma_f32 v11, v11, v11, v13
	v_lshlrev_b32_e32 v12, 16, v60
	v_add_f32_e32 v51, v10, v11
	v_lshlrev_b32_e32 v10, 16, v92
	v_and_b32_e32 v11, 0xffff0000, v92
	v_and_b32_e32 v13, 0xffff0000, v60
	v_add_f32_e32 v10, v10, v12
	v_add_f32_e32 v11, v11, v13
	v_lshlrev_b32_e32 v12, 16, v93
	v_and_b32_e32 v13, 0xffff0000, v93
	v_add_f32_e32 v12, v12, v54
	v_add_f32_e32 v13, v13, v55
	v_add_f32_dpp v0, v0, v0 quad_perm:[2,3,0,1] row_mask:0xf bank_mask:0xf bound_ctrl:1
	v_mov_b32_e32 v56, v11
	v_mov_b32_e32 v57, v13
	v_add_f32_dpp v0, v0, v0 row_half_mirror row_mask:0xf bank_mask:0xf bound_ctrl:1
	v_mov_b32_e32 v54, v10
	v_mov_b32_e32 v55, v12
	v_mul_f32_e32 v56, v56, v56
	v_mul_f32_e32 v57, v57, v57
	v_add_f32_dpp v0, v0, v0 row_mirror row_mask:0xf bank_mask:0xf bound_ctrl:1
	v_fma_f32 v54, v54, v54, v56
	v_fma_f32 v55, v55, v55, v57
	v_readlane_b32 s8, v0, 16
	v_readlane_b32 s9, v0, 48
	v_add_f32_e32 v50, v54, v55
	v_readlane_b32 s6, v0, 0
	v_readlane_b32 s7, v0, 32
	v_mov_b32_e32 v54, s8
	v_mov_b32_e32 v55, s9
	v_add_f32_e32 v54, s6, v54
	v_add_f32_e32 v55, s7, v55
	s_mov_b32 s83, 0x80000
	v_add_f32_e32 v0, v54, v55
	v_fmamk_f32 v0, v0, 0x3b800000, v252
	v_cmp_gt_f32_e32 vcc, s55, v0
	v_mul_f32_e32 v54, 0x4f800000, v0
	s_nop 0
	v_cndmask_b32_e32 v0, v0, v54, vcc
	v_sqrt_f32_e32 v54, v0
	s_nop 0
	v_add_u32_e32 v55, -1, v54
	v_fma_f32 v56, -v55, v54, v0
	v_cmp_ge_f32_e64 s[6:7], 0, v56
	v_add_u32_e32 v56, 1, v54
	s_nop 0
	v_cndmask_b32_e64 v55, v54, v55, s[6:7]
	v_fma_f32 v54, -v56, v54, v0
	v_cmp_lt_f32_e64 s[6:7], 0, v54
	s_nop 1
	v_cndmask_b32_e64 v54, v55, v56, s[6:7]
	v_mul_f32_e32 v55, 0x37800000, v54
	v_cndmask_b32_e32 v54, v54, v55, vcc
	v_cmp_class_f32_e32 vcc, v0, v253
	s_nop 1
	v_cndmask_b32_e32 v0, v54, v0, vcc
	v_div_scale_f32 v54, s[6:7], v0, v0, 1.0
	v_rcp_f32_e32 v55, v54
	s_nop 0
	v_fma_f32 v56, -v54, v55, 1.0
	v_fmac_f32_e32 v55, v56, v55
	v_div_scale_f32 v56, vcc, 1.0, v0, 1.0
	v_mul_f32_e32 v57, v56, v55
	v_fma_f32 v60, -v54, v57, v56
	v_fmac_f32_e32 v57, v60, v55
	v_fma_f32 v54, -v54, v57, v56
	v_div_fmas_f32 v54, v54, v55, v57
	v_div_fixup_f32 v0, v54, v0, 1.0
	v_mul_f32_e32 v46, v46, v0
	v_mul_f32_e32 v47, v47, v0
	v_mul_f32_e32 v48, v48, v0
	v_mul_f32_e32 v49, v49, v0
	v_add_f32_dpp v0, v63, v63 quad_perm:[1,0,3,2] row_mask:0xf bank_mask:0xf bound_ctrl:1
	v_lshlrev_b32_e32 v54, 16, v58
	v_and_b32_e32 v55, 0xffff0000, v58
	v_add_f32_dpp v0, v0, v0 quad_perm:[2,3,0,1] row_mask:0xf bank_mask:0xf bound_ctrl:1
	v_lshlrev_b32_e32 v56, 16, v59
	v_and_b32_e32 v57, 0xffff0000, v59
	v_add_f32_dpp v0, v0, v0 row_half_mirror row_mask:0xf bank_mask:0xf bound_ctrl:1
	v_mul_f32_e32 v48, v48, v56
	v_mul_f32_e32 v49, v49, v57
	v_mul_f32_e32 v46, v46, v54
	v_mul_f32_e32 v47, v47, v55
	v_add_f32_dpp v0, v0, v0 row_mirror row_mask:0xf bank_mask:0xf bound_ctrl:1
	v_cvt_pk_bf16_f32 v46, v46, v47
	v_cvt_pk_bf16_f32 v47, v48, v49
	v_readlane_b32 s8, v0, 16
	v_readlane_b32 s9, v0, 48
	global_store_dwordx2 v[2:3], v[46:47], off
	v_readlane_b32 s6, v0, 0
	v_readlane_b32 s7, v0, 32
	v_mov_b32_e32 v46, s8
	v_mov_b32_e32 v47, s9
	v_add_f32_e32 v46, s6, v46
	v_add_f32_e32 v47, s7, v47
	s_nop 0
	v_add_f32_e32 v0, v46, v47
	v_fmamk_f32 v0, v0, 0x3b800000, v252
	v_cmp_gt_f32_e32 vcc, s55, v0
	v_mul_f32_e32 v46, 0x4f800000, v0
	s_nop 0
	v_cndmask_b32_e32 v0, v0, v46, vcc
	v_sqrt_f32_e32 v46, v0
	s_nop 0
	v_add_u32_e32 v47, -1, v46
	v_fma_f32 v48, -v47, v46, v0
	v_cmp_ge_f32_e64 s[6:7], 0, v48
	v_add_u32_e32 v48, 1, v46
	s_nop 0
	v_cndmask_b32_e64 v47, v46, v47, s[6:7]
	v_fma_f32 v46, -v48, v46, v0
	v_cmp_lt_f32_e64 s[6:7], 0, v46
	s_nop 1
	v_cndmask_b32_e64 v46, v47, v48, s[6:7]
	v_mul_f32_e32 v47, 0x37800000, v46
	v_cndmask_b32_e32 v46, v46, v47, vcc
	v_cmp_class_f32_e32 vcc, v0, v253
	s_nop 1
	v_cndmask_b32_e32 v0, v46, v0, vcc
	v_div_scale_f32 v46, s[6:7], v0, v0, 1.0
	v_rcp_f32_e32 v47, v46
	s_nop 0
	v_fma_f32 v48, -v46, v47, 1.0
	v_fmac_f32_e32 v47, v48, v47
	v_div_scale_f32 v48, vcc, 1.0, v0, 1.0
	v_mul_f32_e32 v49, v48, v47
	v_fma_f32 v54, -v46, v49, v48
	v_fmac_f32_e32 v49, v54, v47
	v_fma_f32 v46, -v46, v49, v48
	v_div_fmas_f32 v46, v46, v47, v49
	v_div_fixup_f32 v0, v46, v0, 1.0
	v_mul_f32_e32 v42, v42, v0
	v_mul_f32_e32 v43, v43, v0
	v_mul_f32_e32 v44, v44, v0
	v_mul_f32_e32 v45, v45, v0
	v_add_f32_dpp v0, v64, v64 quad_perm:[1,0,3,2] row_mask:0xf bank_mask:0xf bound_ctrl:1
	v_lshlrev_b32_e32 v46, 16, v38
	v_and_b32_e32 v47, 0xffff0000, v38
	v_add_f32_dpp v0, v0, v0 quad_perm:[2,3,0,1] row_mask:0xf bank_mask:0xf bound_ctrl:1
	v_lshlrev_b32_e32 v38, 16, v39
	v_and_b32_e32 v39, 0xffff0000, v39
	v_add_f32_dpp v0, v0, v0 row_half_mirror row_mask:0xf bank_mask:0xf bound_ctrl:1
	v_mul_f32_e32 v38, v44, v38
	v_mul_f32_e32 v39, v45, v39
	v_mul_f32_e32 v42, v42, v46
	v_mul_f32_e32 v43, v43, v47
	v_add_f32_dpp v0, v0, v0 row_mirror row_mask:0xf bank_mask:0xf bound_ctrl:1
	v_cvt_pk_bf16_f32 v42, v42, v43
	v_readlane_b32 s8, v0, 16
	v_readlane_b32 s9, v0, 48
	v_cvt_pk_bf16_f32 v43, v38, v39
	v_readlane_b32 s6, v0, 0
	v_readlane_b32 s7, v0, 32
	v_mov_b32_e32 v38, s8
	v_mov_b32_e32 v39, s9
	v_add_f32_e32 v38, s6, v38
	v_add_f32_e32 v39, s7, v39
	global_store_dwordx2 v[2:3], v[42:43], off offset:512
	v_add_f32_e32 v0, v38, v39
	v_fmamk_f32 v0, v0, 0x3b800000, v252
	v_cmp_gt_f32_e32 vcc, s55, v0
	v_mul_f32_e32 v38, 0x4f800000, v0
	s_nop 0
	v_cndmask_b32_e32 v0, v0, v38, vcc
	v_sqrt_f32_e32 v38, v0
	s_nop 0
	v_add_u32_e32 v39, -1, v38
	v_fma_f32 v42, -v39, v38, v0
	v_cmp_ge_f32_e64 s[6:7], 0, v42
	v_add_u32_e32 v42, 1, v38
	s_nop 0
	v_cndmask_b32_e64 v39, v38, v39, s[6:7]
	v_fma_f32 v38, -v42, v38, v0
	v_cmp_lt_f32_e64 s[6:7], 0, v38
	s_nop 1
	v_cndmask_b32_e64 v38, v39, v42, s[6:7]
	v_mul_f32_e32 v39, 0x37800000, v38
	v_cndmask_b32_e32 v38, v38, v39, vcc
	v_cmp_class_f32_e32 vcc, v0, v253
	s_nop 1
	v_cndmask_b32_e32 v0, v38, v0, vcc
	v_div_scale_f32 v38, s[6:7], v0, v0, 1.0
	v_rcp_f32_e32 v39, v38
	s_nop 0
	v_fma_f32 v42, -v38, v39, 1.0
	v_fmac_f32_e32 v39, v42, v39
	v_div_scale_f32 v42, vcc, 1.0, v0, 1.0
	v_mul_f32_e32 v43, v42, v39
	v_fma_f32 v44, -v38, v43, v42
	v_fmac_f32_e32 v43, v44, v39
	v_fma_f32 v38, -v38, v43, v42
	v_div_fmas_f32 v38, v38, v39, v43
	v_div_fixup_f32 v0, v38, v0, 1.0
	v_mul_f32_e32 v36, v36, v0
	v_mul_f32_e32 v37, v37, v0
	v_mul_f32_e32 v40, v40, v0
	v_mul_f32_e32 v41, v41, v0
	v_add_f32_dpp v0, v65, v65 quad_perm:[1,0,3,2] row_mask:0xf bank_mask:0xf bound_ctrl:1
	v_lshlrev_b32_e32 v38, 16, v34
	v_and_b32_e32 v39, 0xffff0000, v34
	v_add_f32_dpp v0, v0, v0 quad_perm:[2,3,0,1] row_mask:0xf bank_mask:0xf bound_ctrl:1
	v_lshlrev_b32_e32 v34, 16, v35
	v_and_b32_e32 v35, 0xffff0000, v35
	v_add_f32_dpp v0, v0, v0 row_half_mirror row_mask:0xf bank_mask:0xf bound_ctrl:1
	v_mul_f32_e32 v34, v40, v34
	v_mul_f32_e32 v35, v41, v35
	v_mul_f32_e32 v36, v36, v38
	v_mul_f32_e32 v37, v37, v39
	v_add_f32_dpp v0, v0, v0 row_mirror row_mask:0xf bank_mask:0xf bound_ctrl:1
	v_cvt_pk_bf16_f32 v36, v36, v37
	v_readlane_b32 s8, v0, 16
	v_readlane_b32 s9, v0, 48
	v_cvt_pk_bf16_f32 v37, v34, v35
	v_readlane_b32 s6, v0, 0
	v_readlane_b32 s7, v0, 32
	v_mov_b32_e32 v34, s8
	v_mov_b32_e32 v35, s9
	v_add_f32_e32 v34, s6, v34
	v_add_f32_e32 v35, s7, v35
	global_store_dwordx2 v[2:3], v[36:37], off offset:1024
	v_add_f32_e32 v0, v34, v35
	v_fmamk_f32 v0, v0, 0x3b800000, v252
	v_cmp_gt_f32_e32 vcc, s55, v0
	v_mul_f32_e32 v34, 0x4f800000, v0
	s_nop 0
	v_cndmask_b32_e32 v0, v0, v34, vcc
	v_sqrt_f32_e32 v34, v0
	s_nop 0
	v_add_u32_e32 v35, -1, v34
	v_fma_f32 v36, -v35, v34, v0
	v_cmp_ge_f32_e64 s[6:7], 0, v36
	v_add_u32_e32 v36, 1, v34
	s_nop 0
	v_cndmask_b32_e64 v35, v34, v35, s[6:7]
	v_fma_f32 v34, -v36, v34, v0
	v_cmp_lt_f32_e64 s[6:7], 0, v34
	s_nop 1
	v_cndmask_b32_e64 v34, v35, v36, s[6:7]
	v_mul_f32_e32 v35, 0x37800000, v34
	v_cndmask_b32_e32 v34, v34, v35, vcc
	v_cmp_class_f32_e32 vcc, v0, v253
	s_nop 1
	v_cndmask_b32_e32 v0, v34, v0, vcc
	v_div_scale_f32 v34, s[6:7], v0, v0, 1.0
	v_rcp_f32_e32 v35, v34
	s_nop 0
	v_fma_f32 v36, -v34, v35, 1.0
	v_fmac_f32_e32 v35, v36, v35
	v_div_scale_f32 v36, vcc, 1.0, v0, 1.0
	v_mul_f32_e32 v37, v36, v35
	v_fma_f32 v38, -v34, v37, v36
	v_fmac_f32_e32 v37, v38, v35
	v_fma_f32 v34, -v34, v37, v36
	v_div_fmas_f32 v34, v34, v35, v37
	v_div_fixup_f32 v0, v34, v0, 1.0
	v_mul_f32_e32 v28, v28, v0
	v_mul_f32_e32 v29, v29, v0
	v_mul_f32_e32 v32, v32, v0
	v_mul_f32_e32 v33, v33, v0
	v_add_f32_dpp v0, v53, v53 quad_perm:[1,0,3,2] row_mask:0xf bank_mask:0xf bound_ctrl:1
	v_lshlrev_b32_e32 v34, 16, v30
	v_and_b32_e32 v35, 0xffff0000, v30
	v_add_f32_dpp v0, v0, v0 quad_perm:[2,3,0,1] row_mask:0xf bank_mask:0xf bound_ctrl:1
	v_lshlrev_b32_e32 v30, 16, v31
	v_and_b32_e32 v31, 0xffff0000, v31
	v_add_f32_dpp v0, v0, v0 row_half_mirror row_mask:0xf bank_mask:0xf bound_ctrl:1
	v_mul_f32_e32 v30, v32, v30
	v_mul_f32_e32 v31, v33, v31
	v_mul_f32_e32 v28, v28, v34
	v_mul_f32_e32 v29, v29, v35
	v_add_f32_dpp v0, v0, v0 row_mirror row_mask:0xf bank_mask:0xf bound_ctrl:1
	v_cvt_pk_bf16_f32 v28, v28, v29
	v_cvt_pk_bf16_f32 v29, v30, v31
	v_readlane_b32 s8, v0, 16
	v_readlane_b32 s9, v0, 48
	global_store_dwordx2 v[2:3], v[28:29], off offset:1536
	v_readlane_b32 s6, v0, 0
	v_readlane_b32 s7, v0, 32
	v_mov_b32_e32 v28, s8
	v_mov_b32_e32 v29, s9
	v_add_f32_e32 v28, s6, v28
	v_add_f32_e32 v29, s7, v29
	s_nop 0
	v_add_f32_e32 v0, v28, v29
	v_fmamk_f32 v0, v0, 0x3b800000, v252
	v_cmp_gt_f32_e32 vcc, s55, v0
	v_mul_f32_e32 v28, 0x4f800000, v0
	s_nop 0
	v_cndmask_b32_e32 v0, v0, v28, vcc
	v_sqrt_f32_e32 v28, v0
	s_nop 0
	v_add_u32_e32 v29, -1, v28
	v_fma_f32 v30, -v29, v28, v0
	v_cmp_ge_f32_e64 s[6:7], 0, v30
	v_add_u32_e32 v30, 1, v28
	s_nop 0
	v_cndmask_b32_e64 v29, v28, v29, s[6:7]
	v_fma_f32 v28, -v30, v28, v0
	v_cmp_lt_f32_e64 s[6:7], 0, v28
	s_nop 1
	v_cndmask_b32_e64 v28, v29, v30, s[6:7]
	v_mul_f32_e32 v29, 0x37800000, v28
	v_cndmask_b32_e32 v28, v28, v29, vcc
	v_cmp_class_f32_e32 vcc, v0, v253
	s_nop 1
	v_cndmask_b32_e32 v0, v28, v0, vcc
	v_div_scale_f32 v28, s[6:7], v0, v0, 1.0
	v_rcp_f32_e32 v29, v28
	s_nop 0
	v_fma_f32 v30, -v28, v29, 1.0
	v_fmac_f32_e32 v29, v30, v29
	v_div_scale_f32 v30, vcc, 1.0, v0, 1.0
	v_mul_f32_e32 v31, v30, v29
	v_fma_f32 v32, -v28, v31, v30
	v_fmac_f32_e32 v31, v32, v29
	v_fma_f32 v28, -v28, v31, v30
	v_div_fmas_f32 v28, v28, v29, v31
	v_div_fixup_f32 v0, v28, v0, 1.0
	v_mul_f32_e32 v22, v22, v0
	v_mul_f32_e32 v23, v23, v0
	v_mul_f32_e32 v24, v24, v0
	v_mul_f32_e32 v25, v25, v0
	v_add_f32_dpp v0, v52, v52 quad_perm:[1,0,3,2] row_mask:0xf bank_mask:0xf bound_ctrl:1
	v_lshlrev_b32_e32 v28, 16, v26
	v_and_b32_e32 v29, 0xffff0000, v26
	v_add_f32_dpp v0, v0, v0 quad_perm:[2,3,0,1] row_mask:0xf bank_mask:0xf bound_ctrl:1
	v_lshlrev_b32_e32 v26, 16, v27
	v_and_b32_e32 v27, 0xffff0000, v27
	v_add_f32_dpp v0, v0, v0 row_half_mirror row_mask:0xf bank_mask:0xf bound_ctrl:1
	v_mul_f32_e32 v24, v24, v26
	v_mul_f32_e32 v25, v25, v27
	v_mul_f32_e32 v22, v22, v28
	v_mul_f32_e32 v23, v23, v29
	v_add_f32_dpp v0, v0, v0 row_mirror row_mask:0xf bank_mask:0xf bound_ctrl:1
	v_cvt_pk_bf16_f32 v22, v22, v23
	v_cvt_pk_bf16_f32 v23, v24, v25
	v_readlane_b32 s8, v0, 16
	v_readlane_b32 s9, v0, 48
	global_store_dwordx2 v[2:3], v[22:23], off offset:2048
	v_readlane_b32 s6, v0, 0
	v_readlane_b32 s7, v0, 32
	v_mov_b32_e32 v22, s8
	v_mov_b32_e32 v23, s9
	v_add_f32_e32 v22, s6, v22
	v_add_f32_e32 v23, s7, v23
	s_nop 0
	v_add_f32_e32 v0, v22, v23
	v_fmamk_f32 v0, v0, 0x3b800000, v252
	v_cmp_gt_f32_e32 vcc, s55, v0
	v_mul_f32_e32 v22, 0x4f800000, v0
	s_nop 0
	v_cndmask_b32_e32 v0, v0, v22, vcc
	v_sqrt_f32_e32 v22, v0
	s_nop 0
	v_add_u32_e32 v23, -1, v22
	v_fma_f32 v24, -v23, v22, v0
	v_cmp_ge_f32_e64 s[6:7], 0, v24
	v_add_u32_e32 v24, 1, v22
	s_nop 0
	v_cndmask_b32_e64 v23, v22, v23, s[6:7]
	v_fma_f32 v22, -v24, v22, v0
	v_cmp_lt_f32_e64 s[6:7], 0, v22
	s_nop 1
	v_cndmask_b32_e64 v22, v23, v24, s[6:7]
	v_mul_f32_e32 v23, 0x37800000, v22
	v_cndmask_b32_e32 v22, v22, v23, vcc
	v_cmp_class_f32_e32 vcc, v0, v253
	s_nop 1
	v_cndmask_b32_e32 v0, v22, v0, vcc
	v_div_scale_f32 v22, s[6:7], v0, v0, 1.0
	v_rcp_f32_e32 v23, v22
	s_nop 0
	v_fma_f32 v24, -v22, v23, 1.0
	v_fmac_f32_e32 v23, v24, v23
	v_div_scale_f32 v24, vcc, 1.0, v0, 1.0
	v_mul_f32_e32 v25, v24, v23
	v_fma_f32 v26, -v22, v25, v24
	v_fmac_f32_e32 v25, v26, v23
	v_fma_f32 v22, -v22, v25, v24
	v_div_fmas_f32 v22, v22, v23, v25
	v_div_fixup_f32 v0, v22, v0, 1.0
	v_mul_f32_e32 v18, v18, v0
	v_mul_f32_e32 v19, v19, v0
	v_mul_f32_e32 v20, v20, v0
	v_mul_f32_e32 v21, v21, v0
	v_add_f32_dpp v0, v51, v51 quad_perm:[1,0,3,2] row_mask:0xf bank_mask:0xf bound_ctrl:1
	v_lshlrev_b32_e32 v22, 16, v8
	v_and_b32_e32 v23, 0xffff0000, v8
	v_add_f32_dpp v0, v0, v0 quad_perm:[2,3,0,1] row_mask:0xf bank_mask:0xf bound_ctrl:1
	v_lshlrev_b32_e32 v8, 16, v9
	v_and_b32_e32 v9, 0xffff0000, v9
	v_add_f32_dpp v0, v0, v0 row_half_mirror row_mask:0xf bank_mask:0xf bound_ctrl:1
	v_mul_f32_e32 v8, v20, v8
	v_mul_f32_e32 v9, v21, v9
	v_mul_f32_e32 v18, v18, v22
	v_mul_f32_e32 v19, v19, v23
	v_add_f32_dpp v0, v0, v0 row_mirror row_mask:0xf bank_mask:0xf bound_ctrl:1
	v_cvt_pk_bf16_f32 v18, v18, v19
	v_readlane_b32 s8, v0, 16
	v_readlane_b32 s9, v0, 48
	v_cvt_pk_bf16_f32 v19, v8, v9
	v_readlane_b32 s6, v0, 0
	v_readlane_b32 s7, v0, 32
	v_mov_b32_e32 v8, s8
	v_mov_b32_e32 v9, s9
	v_add_f32_e32 v8, s6, v8
	v_add_f32_e32 v9, s7, v9
	global_store_dwordx2 v[2:3], v[18:19], off offset:2560
	v_add_f32_e32 v0, v8, v9
	v_fmamk_f32 v0, v0, 0x3b800000, v252
	v_cmp_gt_f32_e32 vcc, s55, v0
	v_mul_f32_e32 v8, 0x4f800000, v0
	s_nop 0
	v_cndmask_b32_e32 v0, v0, v8, vcc
	v_sqrt_f32_e32 v8, v0
	s_nop 0
	v_add_u32_e32 v9, -1, v8
	v_fma_f32 v18, -v9, v8, v0
	v_cmp_ge_f32_e64 s[6:7], 0, v18
	v_add_u32_e32 v18, 1, v8
	s_nop 0
	v_cndmask_b32_e64 v9, v8, v9, s[6:7]
	v_fma_f32 v8, -v18, v8, v0
	v_cmp_lt_f32_e64 s[6:7], 0, v8
	s_nop 1
	v_cndmask_b32_e64 v8, v9, v18, s[6:7]
	v_mul_f32_e32 v9, 0x37800000, v8
	v_cndmask_b32_e32 v8, v8, v9, vcc
	v_cmp_class_f32_e32 vcc, v0, v253
	s_nop 1
	v_cndmask_b32_e32 v0, v8, v0, vcc
	v_div_scale_f32 v8, s[6:7], v0, v0, 1.0
	v_rcp_f32_e32 v9, v8
	s_nop 0
	v_fma_f32 v18, -v8, v9, 1.0
	v_fmac_f32_e32 v9, v18, v9
	v_div_scale_f32 v18, vcc, 1.0, v0, 1.0
	v_mul_f32_e32 v19, v18, v9
	v_fma_f32 v20, -v8, v19, v18
	v_fmac_f32_e32 v19, v20, v9
	v_fma_f32 v8, -v8, v19, v18
	v_div_fmas_f32 v8, v8, v9, v19
	v_div_fixup_f32 v0, v8, v0, 1.0
	v_mul_f32_e32 v14, v14, v0
	v_mul_f32_e32 v15, v15, v0
	v_mul_f32_e32 v16, v16, v0
	v_mul_f32_e32 v17, v17, v0
	v_add_f32_dpp v0, v50, v50 quad_perm:[1,0,3,2] row_mask:0xf bank_mask:0xf bound_ctrl:1
	v_lshlrev_b32_e32 v8, 16, v6
	v_and_b32_e32 v9, 0xffff0000, v6
	v_add_f32_dpp v0, v0, v0 quad_perm:[2,3,0,1] row_mask:0xf bank_mask:0xf bound_ctrl:1
	v_lshlrev_b32_e32 v6, 16, v7
	v_and_b32_e32 v7, 0xffff0000, v7
	v_add_f32_dpp v0, v0, v0 row_half_mirror row_mask:0xf bank_mask:0xf bound_ctrl:1
	v_mul_f32_e32 v6, v16, v6
	v_mul_f32_e32 v7, v17, v7
	v_mul_f32_e32 v8, v14, v8
	v_mul_f32_e32 v9, v15, v9
	v_add_f32_dpp v0, v0, v0 row_mirror row_mask:0xf bank_mask:0xf bound_ctrl:1
	v_cvt_pk_bf16_f32 v8, v8, v9
	v_readlane_b32 s8, v0, 16
	v_readlane_b32 s9, v0, 48
	v_cvt_pk_bf16_f32 v9, v6, v7
	v_readlane_b32 s6, v0, 0
	v_readlane_b32 s7, v0, 32
	v_mov_b32_e32 v6, s8
	v_mov_b32_e32 v7, s9
	v_add_f32_e32 v6, s6, v6
	v_add_f32_e32 v7, s7, v7
	global_store_dwordx2 v[2:3], v[8:9], off offset:3072
	v_add_f32_e32 v0, v6, v7
	v_fmamk_f32 v0, v0, 0x3b800000, v252
	v_cmp_gt_f32_e32 vcc, s55, v0
	v_mul_f32_e32 v6, 0x4f800000, v0
	s_nop 0
	v_cndmask_b32_e32 v0, v0, v6, vcc
	v_sqrt_f32_e32 v6, v0
	s_nop 0
	v_add_u32_e32 v7, -1, v6
	v_fma_f32 v8, -v7, v6, v0
	v_cmp_ge_f32_e64 s[6:7], 0, v8
	v_add_u32_e32 v8, 1, v6
	s_nop 0
	v_cndmask_b32_e64 v7, v6, v7, s[6:7]
	v_fma_f32 v6, -v8, v6, v0
	v_cmp_lt_f32_e64 s[6:7], 0, v6
	s_nop 1
	v_cndmask_b32_e64 v6, v7, v8, s[6:7]
	v_mul_f32_e32 v7, 0x37800000, v6
	v_cndmask_b32_e32 v6, v6, v7, vcc
	v_cmp_class_f32_e32 vcc, v0, v253
	s_nop 1
	v_cndmask_b32_e32 v0, v6, v0, vcc
	v_div_scale_f32 v6, s[6:7], v0, v0, 1.0
	v_rcp_f32_e32 v7, v6
	s_nop 0
	v_fma_f32 v8, -v6, v7, 1.0
	v_fmac_f32_e32 v7, v8, v7
	v_div_scale_f32 v8, vcc, 1.0, v0, 1.0
	v_mul_f32_e32 v9, v8, v7
	v_fma_f32 v14, -v6, v9, v8
	v_fmac_f32_e32 v9, v14, v7
	v_fma_f32 v6, -v6, v9, v8
	v_div_fmas_f32 v6, v6, v7, v9
	v_div_fixup_f32 v0, v6, v0, 1.0
	s_waitcnt vmcnt(23)
	v_lshlrev_b32_e32 v6, 16, v4
	v_and_b32_e32 v7, 0xffff0000, v4
	v_lshlrev_b32_e32 v4, 16, v5
	v_and_b32_e32 v5, 0xffff0000, v5
	v_mul_f32_e32 v8, v10, v0
	v_mul_f32_e32 v9, v11, v0
	v_mul_f32_e32 v10, v12, v0
	v_mul_f32_e32 v11, v13, v0
	v_mul_f32_e32 v6, v8, v6
	v_mul_f32_e32 v7, v9, v7
	v_mul_f32_e32 v4, v10, v4
	v_mul_f32_e32 v5, v11, v5
	v_cvt_pk_bf16_f32 v6, v6, v7
	v_cvt_pk_bf16_f32 v7, v4, v5
	global_store_dwordx2 v[2:3], v[6:7], off offset:3584

;     __host__ __device__ bool next(int i, Unit& u) const { return StaticOrder::next(i >> 1, u); }
;     __device__ __forceinline__ bool next(int i, Unit& u) const { const int s = i * G + c; if (s >= 128) return false; const int t = s >> 2; u.pm = pm0 + (t & 3); u.pn = t >> 2; u.k0 = (s & 3) * ksub; return true; }
; #define PG8_WAIT_V(n) asm volatile("s_waitcnt vmcnt(" #n ")" ::: "memory")
; template <class Epi, class Sched, bool ALIGN_EPI = false, bool SP2 = false>
; __device__ __forceinline__ void gemm_phase(PG8_LAS unsigned char* lds, const Gemm g, const Sched& S, const Epi& E) {
;     ...
;     for (;;) {
;         const bool has_next = S.next(ui + 1, nxt);
;         const char* nA = has_next ? (const char*)g.A + (size_t)nxt.pm * tsA + (size_t)nxt.k0 * 2 : cA; const char* nB = has_next ? (const char*)g.Bt + (size_t)nxt.pn * tsB + (size_t)nxt.k0 * 2 : cB;
;         for (int t = (DRO && ui > 0) ? 2 : 0; t < nt; t += 2) {
;             const bool last = (t == nt - 2);
;             const char* a1 = cA + (size_t)(t + 1) * kstep;
;             const char* a2 = last ? nA : cA + (size_t)(t + 2) * kstep; const char* b2 = last ? nB : cB + (size_t)(t + 2) * kstep;
;             const char* a3 = a2 + kstep; const char* b3 = b2 + kstep;
;             if (last && has_next) S.a_ready(nxt);
;             if constexpr (SP2) {
;             PG8_TRIP(true, PG8_WAIT_V(8));
.LBB0_932:
	v_add_u32_e32 v0, 0x10000, v186
	v_add_u32_e32 v188, 0x14000, v186
	ds_read_b128 v[112:115], v0
	ds_read_b128 v[120:123], v0 offset:1024
	ds_read_b128 v[124:127], v0 offset:2048
	ds_read_b128 v[128:131], v0 offset:3072
	ds_read_b128 v[148:151], v188
	ds_read_b128 v[152:155], v188 offset:1024
	ds_read_b128 v[156:159], v188 offset:2048
	ds_read_b128 v[160:163], v188 offset:3072
	s_add_u32 s20, s18, 0xfff80080
	s_addc_u32 s21, s19, -1
	s_cmp_eq_u32 s78, 28
	s_cselect_b32 s24, s7, s20
	s_cselect_b32 s25, s6, s21
	s_cselect_b32 s22, s11, s79
	s_cselect_b32 s23, s9, s82
	s_add_u32 s20, s24, 0x80
	s_addc_u32 s21, s25, 0
	ds_read_b128 v[164:167], v187
	ds_read_b128 v[168:171], v187 offset:1024
	ds_read_b128 v[178:181], v187 offset:2048
	ds_read_b128 v[190:193], v187 offset:3072
	ds_read_b128 v[194:197], v187 offset:4096
	ds_read_b128 v[198:201], v187 offset:5120
	ds_read_b128 v[202:205], v187 offset:6144
	ds_read_b128 v[206:209], v187 offset:7168
	s_mov_b32 m0, s57
	s_nop 0
	global_load_lds_dwordx4 v174, s[18:19]
	s_nop 0
	s_mov_b32 m0, s63
	s_nop 0
	global_load_lds_dwordx4 v176, s[18:19]
	s_waitcnt vmcnt(8)
	s_waitcnt lgkmcnt(0)
	s_barrier
	s_setprio 1
	s_waitcnt lgkmcnt(0)
	v_mfma_f32_16x16x32_bf16 v[144:147], v[112:115], v[164:167], v[144:147]
	v_mfma_f32_16x16x32_bf16 v[140:143], v[124:127], v[164:167], v[140:143]
	s_waitcnt lgkmcnt(5)
	v_mfma_f32_16x16x32_bf16 v[116:119], v[112:115], v[178:181], v[116:119]
	v_mfma_f32_16x16x32_bf16 v[108:111], v[124:127], v[178:181], v[108:111]
	s_waitcnt lgkmcnt(3)
	v_mfma_f32_16x16x32_bf16 v[96:99], v[112:115], v[194:197], v[96:99]
	v_mfma_f32_16x16x32_bf16 v[92:95], v[124:127], v[194:197], v[92:95]
	s_waitcnt lgkmcnt(1)
	v_mfma_f32_16x16x32_bf16 v[80:83], v[112:115], v[202:205], v[80:83]
	v_mfma_f32_16x16x32_bf16 v[76:79], v[124:127], v[202:205], v[76:79]
	v_mfma_f32_16x16x32_bf16 v[144:147], v[120:123], v[168:171], v[144:147]
	v_mfma_f32_16x16x32_bf16 v[140:143], v[128:131], v[168:171], v[140:143]
	v_mfma_f32_16x16x32_bf16 v[116:119], v[120:123], v[190:193], v[116:119]
	v_mfma_f32_16x16x32_bf16 v[108:111], v[128:131], v[190:193], v[108:111]
	v_mfma_f32_16x16x32_bf16 v[96:99], v[120:123], v[198:201], v[96:99]
	v_mfma_f32_16x16x32_bf16 v[92:95], v[128:131], v[198:201], v[92:95]
	s_waitcnt lgkmcnt(0)
	v_mfma_f32_16x16x32_bf16 v[80:83], v[120:123], v[206:209], v[80:83]
	v_mfma_f32_16x16x32_bf16 v[76:79], v[128:131], v[206:209], v[76:79]
	s_setprio 0
	s_setprio 1
	v_mfma_f32_16x16x32_bf16 v[136:139], v[148:151], v[164:167], v[136:139]
	v_mfma_f32_16x16x32_bf16 v[132:135], v[156:159], v[164:167], v[132:135]
	v_mfma_f32_16x16x32_bf16 v[104:107], v[148:151], v[178:181], v[104:107]
	v_mfma_f32_16x16x32_bf16 v[100:103], v[156:159], v[178:181], v[100:103]
	v_mfma_f32_16x16x32_bf16 v[88:91], v[148:151], v[194:197], v[88:91]
	v_mfma_f32_16x16x32_bf16 v[84:87], v[156:159], v[194:197], v[84:87]
	v_mfma_f32_16x16x32_bf16 v[72:75], v[148:151], v[202:205], v[72:75]
	v_mfma_f32_16x16x32_bf16 v[68:71], v[156:159], v[202:205], v[68:71]
	v_mfma_f32_16x16x32_bf16 v[136:139], v[152:155], v[168:171], v[136:139]
	v_mfma_f32_16x16x32_bf16 v[132:135], v[160:163], v[168:171], v[132:135]
	v_mfma_f32_16x16x32_bf16 v[104:107], v[152:155], v[190:193], v[104:107]
	v_mfma_f32_16x16x32_bf16 v[100:103], v[160:163], v[190:193], v[100:103]
	v_mfma_f32_16x16x32_bf16 v[88:91], v[152:155], v[198:201], v[88:91]
	v_mfma_f32_16x16x32_bf16 v[84:87], v[160:163], v[198:201], v[84:87]
	v_mfma_f32_16x16x32_bf16 v[72:75], v[152:155], v[206:209], v[72:75]
	v_mfma_f32_16x16x32_bf16 v[68:71], v[160:163], v[206:209], v[68:71]
	s_setprio 0
	s_barrier
	ds_read_b128 v[164:167], v187 offset:16384
	ds_read_b128 v[168:171], v187 offset:17408
	ds_read_b128 v[178:181], v187 offset:18432
	ds_read_b128 v[190:193], v187 offset:19456
	ds_read_b128 v[194:197], v187 offset:20480
	ds_read_b128 v[198:201], v187 offset:21504
	ds_read_b128 v[202:205], v187 offset:22528
	ds_read_b128 v[206:209], v187 offset:23552
	s_mov_b32 m0, s28
	s_nop 0
	global_load_lds_dwordx4 v175, s[22:23]
	s_add_u32 s88, s22, 0x80000
	s_mov_b32 m0, s29
	s_nop 0
	global_load_lds_dwordx4 v177, s[22:23]
	s_addc_u32 s89, s23, 0
	s_mov_b32 m0, s30
	s_nop 0
	global_load_lds_dwordx4 v175, s[88:89]
	s_nop 0
	s_mov_b32 m0, s31
	s_nop 0
	global_load_lds_dwordx4 v177, s[88:89]
	s_nop 0
	s_mov_b32 m0, s27
	s_nop 0
	global_load_lds_dwordx4 v174, s[24:25]
	s_nop 0
	s_mov_b32 m0, s35
	s_nop 0
	global_load_lds_dwordx4 v176, s[24:25]
	s_waitcnt vmcnt(8)
	s_waitcnt lgkmcnt(0)
	s_barrier
	s_setprio 1
	s_waitcnt lgkmcnt(0)
	v_mfma_f32_16x16x32_bf16 v[64:67], v[112:115], v[164:167], v[64:67]
	v_mfma_f32_16x16x32_bf16 v[60:63], v[124:127], v[164:167], v[60:63]
	s_waitcnt lgkmcnt(5)
	v_mfma_f32_16x16x32_bf16 v[48:51], v[112:115], v[178:181], v[48:51]
	v_mfma_f32_16x16x32_bf16 v[44:47], v[124:127], v[178:181], v[44:47]
	s_waitcnt lgkmcnt(3)
	v_mfma_f32_16x16x32_bf16 v[32:35], v[112:115], v[194:197], v[32:35]
	v_mfma_f32_16x16x32_bf16 v[28:31], v[124:127], v[194:197], v[28:31]
	s_waitcnt lgkmcnt(1)
	v_mfma_f32_16x16x32_bf16 v[16:19], v[112:115], v[202:205], v[16:19]
	v_mfma_f32_16x16x32_bf16 v[12:15], v[124:127], v[202:205], v[12:15]
	v_mfma_f32_16x16x32_bf16 v[64:67], v[120:123], v[168:171], v[64:67]
	v_mfma_f32_16x16x32_bf16 v[60:63], v[128:131], v[168:171], v[60:63]
	v_mfma_f32_16x16x32_bf16 v[48:51], v[120:123], v[190:193], v[48:51]
	v_mfma_f32_16x16x32_bf16 v[44:47], v[128:131], v[190:193], v[44:47]
	v_mfma_f32_16x16x32_bf16 v[32:35], v[120:123], v[198:201], v[32:35]
	v_mfma_f32_16x16x32_bf16 v[28:31], v[128:131], v[198:201], v[28:31]
	s_waitcnt lgkmcnt(0)
	v_mfma_f32_16x16x32_bf16 v[16:19], v[120:123], v[206:209], v[16:19]
	v_mfma_f32_16x16x32_bf16 v[12:15], v[128:131], v[206:209], v[12:15]
	s_setprio 0
	s_setprio 1
	v_mfma_f32_16x16x32_bf16 v[56:59], v[148:151], v[164:167], v[56:59]
	v_mfma_f32_16x16x32_bf16 v[52:55], v[156:159], v[164:167], v[52:55]
	v_mfma_f32_16x16x32_bf16 v[40:43], v[148:151], v[178:181], v[40:43]
	v_mfma_f32_16x16x32_bf16 v[36:39], v[156:159], v[178:181], v[36:39]
	v_mfma_f32_16x16x32_bf16 v[24:27], v[148:151], v[194:197], v[24:27]
	v_mfma_f32_16x16x32_bf16 v[20:23], v[156:159], v[194:197], v[20:23]
	v_mfma_f32_16x16x32_bf16 v[8:11], v[148:151], v[202:205], v[8:11]
	v_mfma_f32_16x16x32_bf16 v[2:5], v[156:159], v[202:205], v[4:7]
	v_mfma_f32_16x16x32_bf16 v[56:59], v[152:155], v[168:171], v[56:59]
	v_mfma_f32_16x16x32_bf16 v[52:55], v[160:163], v[168:171], v[52:55]
	v_mfma_f32_16x16x32_bf16 v[40:43], v[152:155], v[190:193], v[40:43]
	v_mfma_f32_16x16x32_bf16 v[36:39], v[160:163], v[190:193], v[36:39]
	v_mfma_f32_16x16x32_bf16 v[24:27], v[152:155], v[198:201], v[24:27]
	v_mfma_f32_16x16x32_bf16 v[20:23], v[160:163], v[198:201], v[20:23]
	v_mfma_f32_16x16x32_bf16 v[8:11], v[152:155], v[206:209], v[8:11]
	v_mfma_f32_16x16x32_bf16 v[2:5], v[160:163], v[206:209], v[2:5]
	s_setprio 0
	s_barrier
	v_add_u32_e32 v189, 0x18000, v186
	v_add_u32_e32 v190, 0x1c000, v186
	ds_read_b128 v[112:115], v189
	ds_read_b128 v[120:123], v189 offset:1024
	ds_read_b128 v[124:127], v189 offset:2048
	ds_read_b128 v[128:131], v189 offset:3072
	ds_read_b128 v[148:151], v190
	ds_read_b128 v[152:155], v190 offset:1024
	ds_read_b128 v[156:159], v190 offset:2048
	ds_read_b128 v[160:163], v190 offset:3072
	ds_read_b128 v[164:167], v187 offset:32768
	ds_read_b128 v[168:171], v187 offset:33792
	ds_read_b128 v[178:181], v187 offset:34816
	ds_read_b128 v[192:195], v187 offset:35840
	ds_read_b128 v[196:199], v187 offset:36864
	ds_read_b128 v[200:203], v187 offset:37888
	ds_read_b128 v[204:207], v187 offset:38912
	ds_read_b128 v[208:211], v187 offset:39936
	s_add_u32 s24, s24, 0x80000
	s_addc_u32 s25, s25, 0
	s_mov_b32 m0, s36
	s_nop 0
	global_load_lds_dwordx4 v174, s[24:25]
	s_nop 0
	s_mov_b32 m0, s37
	s_nop 0
	global_load_lds_dwordx4 v176, s[24:25]
	s_waitcnt vmcnt(8)
	s_waitcnt lgkmcnt(0)
	s_barrier
	s_setprio 1
	s_waitcnt lgkmcnt(0)
	v_mfma_f32_16x16x32_bf16 v[144:147], v[112:115], v[164:167], v[144:147]
	v_mfma_f32_16x16x32_bf16 v[140:143], v[124:127], v[164:167], v[140:143]
	s_waitcnt lgkmcnt(5)
	v_mfma_f32_16x16x32_bf16 v[116:119], v[112:115], v[178:181], v[116:119]
	v_mfma_f32_16x16x32_bf16 v[108:111], v[124:127], v[178:181], v[108:111]
	s_waitcnt lgkmcnt(3)
	v_mfma_f32_16x16x32_bf16 v[96:99], v[112:115], v[196:199], v[96:99]
	v_mfma_f32_16x16x32_bf16 v[92:95], v[124:127], v[196:199], v[92:95]
	s_waitcnt lgkmcnt(1)
	v_mfma_f32_16x16x32_bf16 v[80:83], v[112:115], v[204:207], v[80:83]
	v_mfma_f32_16x16x32_bf16 v[76:79], v[124:127], v[204:207], v[76:79]
	v_mfma_f32_16x16x32_bf16 v[144:147], v[120:123], v[168:171], v[144:147]
	v_mfma_f32_16x16x32_bf16 v[140:143], v[128:131], v[168:171], v[140:143]
	v_mfma_f32_16x16x32_bf16 v[116:119], v[120:123], v[192:195], v[116:119]
	v_mfma_f32_16x16x32_bf16 v[108:111], v[128:131], v[192:195], v[108:111]
	v_mfma_f32_16x16x32_bf16 v[96:99], v[120:123], v[200:203], v[96:99]
	v_mfma_f32_16x16x32_bf16 v[92:95], v[128:131], v[200:203], v[92:95]
	s_waitcnt lgkmcnt(0)
	v_mfma_f32_16x16x32_bf16 v[80:83], v[120:123], v[208:211], v[80:83]
	v_mfma_f32_16x16x32_bf16 v[76:79], v[128:131], v[208:211], v[76:79]
	s_setprio 0
	s_setprio 1
	v_mfma_f32_16x16x32_bf16 v[136:139], v[148:151], v[164:167], v[136:139]
	v_mfma_f32_16x16x32_bf16 v[132:135], v[156:159], v[164:167], v[132:135]
	v_mfma_f32_16x16x32_bf16 v[104:107], v[148:151], v[178:181], v[104:107]
	v_mfma_f32_16x16x32_bf16 v[100:103], v[156:159], v[178:181], v[100:103]
	v_mfma_f32_16x16x32_bf16 v[88:91], v[148:151], v[196:199], v[88:91]
	v_mfma_f32_16x16x32_bf16 v[84:87], v[156:159], v[196:199], v[84:87]
	v_mfma_f32_16x16x32_bf16 v[72:75], v[148:151], v[204:207], v[72:75]
	v_mfma_f32_16x16x32_bf16 v[68:71], v[156:159], v[204:207], v[68:71]
	v_mfma_f32_16x16x32_bf16 v[136:139], v[152:155], v[168:171], v[136:139]
	v_mfma_f32_16x16x32_bf16 v[132:135], v[160:163], v[168:171], v[132:135]
	v_mfma_f32_16x16x32_bf16 v[104:107], v[152:155], v[192:195], v[104:107]
	v_mfma_f32_16x16x32_bf16 v[100:103], v[160:163], v[192:195], v[100:103]
	v_mfma_f32_16x16x32_bf16 v[88:91], v[152:155], v[200:203], v[88:91]
	v_mfma_f32_16x16x32_bf16 v[84:87], v[160:163], v[200:203], v[84:87]
	v_mfma_f32_16x16x32_bf16 v[72:75], v[152:155], v[208:211], v[72:75]
	v_mfma_f32_16x16x32_bf16 v[68:71], v[160:163], v[208:211], v[68:71]
	s_setprio 0
	s_barrier
; #define ER_LOAD(dst, ai, mp) do { _Pragma("unroll") for (int mm = 0; mm < 2; ++mm) _Pragma("unroll") for (int bj = 0; bj < 2; ++bj) \
;             dst[mm][bj] = *(const u32x4*)(xb + (size_t)((ai) * HALF + (2 * (mp) + mm) * 16) * 2048 + bj * HALF); } while (0)
;     __device__ __forceinline__ void operator()(const f32x4 (&acc)[2][2][4][2], const Unit& u, int wr, int wc, int fr, int fq) const {
;         const int row0 = u.pm * BM + wr * 64 + fr, col0 = u.pn * BM + wc * 32 + 8 * fq;
;         const int b = (u.pm < n_lat_panels) ? (u.pm >> 4) : 4;
;         const float* g = gate + (size_t)b * gstride + col0;
;         bf16_t* xb = X + (size_t)row0 * 2048 + col0;
;         f32x4 gv[2][2];
; #pragma unroll
;         for (int bj = 0; bj < 2; ++bj)
; #pragma unroll
;             for (int n = 0; n < 2; ++n) gv[bj][n] = *(const f32x4*)(g + bj * HALF + 4 * n);
;         u32x4 xa[2][2], xc[2][2];
;     ...
;         ER_LOAD(xa, 0, 0); ER_LOAD(xc, 0, 1);
	ds_read_b128 v[164:167], v187 offset:49152
	ds_read_b128 v[168:171], v187 offset:50176
	ds_read_b128 v[178:181], v187 offset:51200
	ds_read_b128 v[192:195], v187 offset:52224
	ds_read_b128 v[196:199], v187 offset:53248
	ds_read_b128 v[200:203], v187 offset:54272
	ds_read_b128 v[204:207], v187 offset:55296
	ds_read_b128 v[208:211], v187 offset:56320
	s_add_u32 s24, s22, 0x80
	s_addc_u32 s25, s23, 0
	s_mov_b32 m0, s44
	s_nop 0
	global_load_lds_dwordx4 v175, s[24:25]
	s_add_u32 s22, s22, 0x80080
	s_mov_b32 m0, s48
	s_nop 0
	global_load_lds_dwordx4 v177, s[24:25]
	s_addc_u32 s23, s23, 0
	s_mov_b32 m0, s52
	s_nop 0
	global_load_lds_dwordx4 v175, s[22:23]
	s_nop 0
	s_mov_b32 m0, s53
	s_nop 0
	global_load_lds_dwordx4 v177, s[22:23]
	s_nop 0
	s_mov_b32 m0, s49
	s_nop 0
	global_load_lds_dwordx4 v174, s[20:21]
	s_nop 0
	s_mov_b32 m0, s51
	s_nop 0
	global_load_lds_dwordx4 v176, s[20:21]
	s_waitcnt vmcnt(8)
	s_waitcnt lgkmcnt(0)
	s_barrier
	s_setprio 1
	s_waitcnt lgkmcnt(0)
	v_mfma_f32_16x16x32_bf16 v[64:67], v[112:115], v[164:167], v[64:67]
	v_mfma_f32_16x16x32_bf16 v[60:63], v[124:127], v[164:167], v[60:63]
	s_waitcnt lgkmcnt(5)
	v_mfma_f32_16x16x32_bf16 v[48:51], v[112:115], v[178:181], v[48:51]
	v_mfma_f32_16x16x32_bf16 v[44:47], v[124:127], v[178:181], v[44:47]
	s_waitcnt lgkmcnt(3)
	v_mfma_f32_16x16x32_bf16 v[32:35], v[112:115], v[196:199], v[32:35]
	v_mfma_f32_16x16x32_bf16 v[28:31], v[124:127], v[196:199], v[28:31]
	s_waitcnt lgkmcnt(1)
	v_mfma_f32_16x16x32_bf16 v[16:19], v[112:115], v[204:207], v[16:19]
	v_mfma_f32_16x16x32_bf16 v[12:15], v[124:127], v[204:207], v[12:15]
	v_mfma_f32_16x16x32_bf16 v[64:67], v[120:123], v[168:171], v[64:67]
	v_mfma_f32_16x16x32_bf16 v[60:63], v[128:131], v[168:171], v[60:63]
	v_mfma_f32_16x16x32_bf16 v[48:51], v[120:123], v[192:195], v[48:51]
	v_mfma_f32_16x16x32_bf16 v[44:47], v[128:131], v[192:195], v[44:47]
	v_mfma_f32_16x16x32_bf16 v[32:35], v[120:123], v[200:203], v[32:35]
	v_mfma_f32_16x16x32_bf16 v[28:31], v[128:131], v[200:203], v[28:31]
	s_waitcnt lgkmcnt(0)
	v_mfma_f32_16x16x32_bf16 v[16:19], v[120:123], v[208:211], v[16:19]
	v_mfma_f32_16x16x32_bf16 v[12:15], v[128:131], v[208:211], v[12:15]
	s_setprio 0
	s_setprio 1
	v_mfma_f32_16x16x32_bf16 v[56:59], v[148:151], v[164:167], v[56:59]
	v_mfma_f32_16x16x32_bf16 v[52:55], v[156:159], v[164:167], v[52:55]
	v_mfma_f32_16x16x32_bf16 v[40:43], v[148:151], v[178:181], v[40:43]
	v_mfma_f32_16x16x32_bf16 v[36:39], v[156:159], v[178:181], v[36:39]
	v_mfma_f32_16x16x32_bf16 v[24:27], v[148:151], v[196:199], v[24:27]
	v_mfma_f32_16x16x32_bf16 v[20:23], v[156:159], v[196:199], v[20:23]
	v_mfma_f32_16x16x32_bf16 v[6:9], v[148:151], v[204:207], v[8:11]
	v_mfma_f32_16x16x32_bf16 v[2:5], v[156:159], v[204:207], v[2:5]
	v_mfma_f32_16x16x32_bf16 v[56:59], v[152:155], v[168:171], v[56:59]
	v_mfma_f32_16x16x32_bf16 v[52:55], v[160:163], v[168:171], v[52:55]
	v_mfma_f32_16x16x32_bf16 v[40:43], v[152:155], v[192:195], v[40:43]
	v_mfma_f32_16x16x32_bf16 v[36:39], v[160:163], v[192:195], v[36:39]
	v_mfma_f32_16x16x32_bf16 v[24:27], v[152:155], v[200:203], v[24:27]
	v_mfma_f32_16x16x32_bf16 v[20:23], v[160:163], v[200:203], v[20:23]
	v_mfma_f32_16x16x32_bf16 v[8:11], v[152:155], v[208:211], v[6:9]
	v_mfma_f32_16x16x32_bf16 v[4:7], v[160:163], v[208:211], v[2:5]
	s_setprio 0
	s_barrier
	s_add_i32 s78, s78, 2
	s_add_u32 s79, s79, 0x100
	s_addc_u32 s82, s82, 0
	s_add_u32 s18, s18, 0x100
	s_addc_u32 s19, s19, 0
	s_cmp_gt_u32 s78, 29
	s_cbranch_scc0 .LBB0_932
	s_add_u32 s18, s7, 0x80080
	s_addc_u32 s19, s6, 0
	s_min_i32 s6, s69, 64
	v_lshl_add_u32 v2, s69, 8, v184
	s_ashr_i32 s6, s6, 4
	s_mul_hi_i32 s7, s6, 0xc000
	s_mul_i32 s6, s6, 0xc000
	v_ashrrev_i32_e32 v3, 31, v2
	s_mov_b32 m0, s57
	s_nop 0
	global_load_lds_dwordx4 v174, s[18:19]
	v_lshl_or_b32 v148, s67, 8, v185
	s_add_u32 s6, s40, s6
	v_lshlrev_b64 v[2:3], 12, v[2:3]
	s_mov_b32 m0, s63
	s_nop 0
	global_load_lds_dwordx4 v176, s[18:19]
	s_addc_u32 s7, s41, s7
	v_ashrrev_i32_e32 v149, 31, v148
	v_lshl_add_u64 v[2:3], s[80:81], 0, v[2:3]
	v_lshl_add_u64 v[112:113], v[148:149], 2, s[6:7]
	v_lshl_add_u64 v[2:3], v[148:149], 1, v[2:3]
	global_load_dwordx4 v[128:131], v[112:113], off
	global_load_dwordx4 v[124:127], v[112:113], off offset:16
	global_load_dwordx4 v[120:123], v[112:113], off offset:512
	global_load_dwordx4 v[112:115], v[112:113], off offset:528
	global_load_dwordx4 v[178:181], v[2:3], off
	global_load_dwordx4 v[192:195], v[2:3], off offset:256
	v_add_co_u32_e32 v172, vcc, 0x10000, v2
	s_nop 1
	v_addc_co_u32_e32 v173, vcc, 0, v3, vcc
	global_load_dwordx4 v[196:199], v[172:173], off
	global_load_dwordx4 v[164:167], v[172:173], off offset:256
	v_add_co_u32_e32 v170, vcc, 0x20000, v2
	s_nop 1
	v_addc_co_u32_e32 v171, vcc, 0, v3, vcc
	global_load_dwordx4 v[160:163], v[170:171], off
	global_load_dwordx4 v[156:159], v[170:171], off offset:256
	v_add_co_u32_e32 v168, vcc, 0x30000, v2
	s_nop 1
	v_addc_co_u32_e32 v169, vcc, 0, v3, vcc
	global_load_dwordx4 v[152:155], v[168:169], off
	global_load_dwordx4 v[148:151], v[168:169], off offset:256
	v_add_co_u32_e32 v244, vcc, 0x80000, v2
	s_nop 1
	v_addc_co_u32_e32 v245, vcc, 0, v3, vcc
	global_load_dwordx4 v[212:215], v[244:245], off
	global_load_dwordx4 v[216:219], v[244:245], off offset:256
	v_add_co_u32_e32 v246, vcc, 0x90000, v2
	s_nop 1
	v_addc_co_u32_e32 v247, vcc, 0, v3, vcc
	global_load_dwordx4 v[220:223], v[246:247], off
	global_load_dwordx4 v[224:227], v[246:247], off offset:256
	v_add_co_u32_e32 v248, vcc, 0xa0000, v2
	s_nop 1
	v_addc_co_u32_e32 v249, vcc, 0, v3, vcc
	global_load_dwordx4 v[228:231], v[248:249], off
	global_load_dwordx4 v[232:235], v[248:249], off offset:256
	v_add_co_u32_e32 v250, vcc, 0xb0000, v2
	s_nop 1
	v_addc_co_u32_e32 v251, vcc, 0, v3, vcc
	global_load_dwordx4 v[236:239], v[250:251], off
	global_load_dwordx4 v[240:243], v[250:251], off offset:256
	s_nop 0
	s_nop 0
	s_mov_b32 s6, 0x10000
	s_mov_b32 s6, 0x90000
	s_nop 0
	s_mov_b64 s[18:19], -1
	s_nop 0
	s_waitcnt vmcnt(15)
; #define ER_LOAD(dst, ai, mp) do { _Pragma("unroll") for (int mm = 0; mm < 2; ++mm) _Pragma("unroll") for (int bj = 0; bj < 2; ++bj) \
;             dst[mm][bj] = *(const u32x4*)(xb + (size_t)((ai) * HALF + (2 * (mp) + mm) * 16) * 2048 + bj * HALF); } while (0)
;     __device__ __forceinline__ void operator()(const f32x4 (&acc)[2][2][4][2], const Unit& u, int wr, int wc, int fr, int fq) const {
;     ...
;         ER_LOAD(xa, 0, 0); ER_LOAD(xc, 0, 1);
;         ER_STORE(xa, 0, 0); ER_LOAD(xa, 1, 0);
;         ER_STORE(xc, 0, 1); ER_LOAD(xc, 1, 1);
;         ER_STORE(xa, 1, 0); ER_STORE(xc, 1, 1);
	v_cvt_f32_f16_e32 v200, v178
	v_cvt_f32_f16_sdwa v201, v178 dst_sel:DWORD dst_unused:UNUSED_PAD src0_sel:WORD_1
	v_cvt_f32_f16_e32 v178, v179
	v_cvt_f32_f16_sdwa v179, v179 dst_sel:DWORD dst_unused:UNUSED_PAD src0_sel:WORD_1
	v_fma_f32 v144, v144, v128, v200
	v_fma_f32 v145, v145, v129, v201
	v_fma_f32 v146, v146, v130, v178
	v_fma_f32 v147, v147, v131, v179
	v_cvt_f32_f16_e32 v178, v180
	v_cvt_f32_f16_sdwa v179, v180 dst_sel:DWORD dst_unused:UNUSED_PAD src0_sel:WORD_1
	v_cvt_f32_f16_e32 v180, v181
	v_cvt_f32_f16_sdwa v181, v181 dst_sel:DWORD dst_unused:UNUSED_PAD src0_sel:WORD_1
	v_fma_f32 v180, v142, v126, v180
	v_fma_f32 v181, v143, v127, v181
	v_fma_f32 v142, v140, v124, v178
	v_fma_f32 v143, v141, v125, v179
	v_cvt_pk_f16_f32 v140, v144, v145
	v_cvt_pk_f16_f32 v141, v146, v147
	v_cvt_pk_f16_f32 v142, v142, v143
	v_cvt_pk_f16_f32 v143, v180, v181
	global_store_dwordx4 v[2:3], v[140:143], off
	s_nop 1
	s_waitcnt vmcnt(15)
	v_cvt_f32_f16_e32 v140, v192
	v_cvt_f32_f16_sdwa v141, v192 dst_sel:DWORD dst_unused:UNUSED_PAD src0_sel:WORD_1
	v_cvt_f32_f16_e32 v142, v193
	v_cvt_f32_f16_sdwa v143, v193 dst_sel:DWORD dst_unused:UNUSED_PAD src0_sel:WORD_1
	v_fma_f32 v136, v136, v120, v140
	v_fma_f32 v137, v137, v121, v141
	v_cvt_f32_f16_e32 v140, v194
	v_fma_f32 v138, v138, v122, v142
	v_fma_f32 v139, v139, v123, v143
	v_cvt_f32_f16_sdwa v141, v194 dst_sel:DWORD dst_unused:UNUSED_PAD src0_sel:WORD_1
	v_cvt_f32_f16_e32 v142, v195
	v_cvt_f32_f16_sdwa v143, v195 dst_sel:DWORD dst_unused:UNUSED_PAD src0_sel:WORD_1
	v_fma_f32 v142, v134, v114, v142
	v_fma_f32 v143, v135, v115, v143
	v_fma_f32 v134, v132, v112, v140
	v_fma_f32 v135, v133, v113, v141
	v_cvt_pk_f16_f32 v132, v136, v137
	v_cvt_pk_f16_f32 v133, v138, v139
	v_cvt_pk_f16_f32 v134, v134, v135
	v_cvt_pk_f16_f32 v135, v142, v143
	global_store_dwordx4 v[2:3], v[132:135], off offset:256
	s_waitcnt vmcnt(13)
	v_cvt_f32_f16_e32 v136, v160
	v_cvt_f32_f16_sdwa v137, v160 dst_sel:DWORD dst_unused:UNUSED_PAD src0_sel:WORD_1
	v_cvt_f32_f16_e32 v132, v196
	v_cvt_f32_f16_sdwa v133, v196 dst_sel:DWORD dst_unused:UNUSED_PAD src0_sel:WORD_1
	v_cvt_f32_f16_e32 v134, v197
	v_cvt_f32_f16_sdwa v135, v197 dst_sel:DWORD dst_unused:UNUSED_PAD src0_sel:WORD_1
	v_cvt_f32_f16_e32 v138, v161
	v_fma_f32 v116, v116, v128, v132
	v_fma_f32 v117, v117, v129, v133
	v_cvt_f32_f16_e32 v132, v198
	v_fma_f32 v118, v118, v130, v134
	v_fma_f32 v119, v119, v131, v135
	v_cvt_f32_f16_sdwa v133, v198 dst_sel:DWORD dst_unused:UNUSED_PAD src0_sel:WORD_1
	v_cvt_f32_f16_e32 v134, v199
	v_cvt_f32_f16_sdwa v135, v199 dst_sel:DWORD dst_unused:UNUSED_PAD src0_sel:WORD_1
	v_cvt_f32_f16_sdwa v139, v161 dst_sel:DWORD dst_unused:UNUSED_PAD src0_sel:WORD_1
	v_fma_f32 v96, v96, v128, v136
	v_fma_f32 v97, v97, v129, v137
	v_cvt_f32_f16_e32 v136, v162
	v_fma_f32 v134, v110, v126, v134
	v_fma_f32 v135, v111, v127, v135
	v_fma_f32 v110, v108, v124, v132
	v_fma_f32 v111, v109, v125, v133
	v_cvt_pk_f16_f32 v108, v116, v117
	v_cvt_pk_f16_f32 v109, v118, v119
	v_cvt_pk_f16_f32 v110, v110, v111
	v_cvt_pk_f16_f32 v111, v134, v135
	global_store_dwordx4 v[172:173], v[108:111], off
	v_add_co_u32_e32 v134, vcc, s83, v2
	s_nop 0
	v_cvt_f32_f16_e32 v108, v164
	v_cvt_f32_f16_sdwa v109, v164 dst_sel:DWORD dst_unused:UNUSED_PAD src0_sel:WORD_1
	v_cvt_f32_f16_e32 v110, v165
	v_cvt_f32_f16_sdwa v111, v165 dst_sel:DWORD dst_unused:UNUSED_PAD src0_sel:WORD_1
	v_addc_co_u32_e32 v135, vcc, 0, v3, vcc
	v_fma_f32 v104, v104, v120, v108
	v_fma_f32 v105, v105, v121, v109
	v_fma_f32 v106, v106, v122, v110
	v_fma_f32 v107, v107, v123, v111
	v_cvt_f32_f16_e32 v108, v166
	v_cvt_f32_f16_sdwa v109, v166 dst_sel:DWORD dst_unused:UNUSED_PAD src0_sel:WORD_1
	v_cvt_f32_f16_e32 v110, v167
	v_cvt_f32_f16_sdwa v111, v167 dst_sel:DWORD dst_unused:UNUSED_PAD src0_sel:WORD_1
	v_fma_f32 v98, v98, v130, v138
	v_fma_f32 v99, v99, v131, v139
	v_cvt_f32_f16_sdwa v137, v162 dst_sel:DWORD dst_unused:UNUSED_PAD src0_sel:WORD_1
	v_cvt_f32_f16_e32 v138, v163
	v_fma_f32 v110, v102, v114, v110
	v_fma_f32 v111, v103, v115, v111
	v_fma_f32 v102, v100, v112, v108
	v_fma_f32 v103, v101, v113, v109
	v_cvt_pk_f16_f32 v100, v104, v105
	v_cvt_pk_f16_f32 v101, v106, v107
	v_cvt_pk_f16_f32 v102, v102, v103
	v_cvt_pk_f16_f32 v103, v110, v111
	global_store_dwordx4 v[172:173], v[100:103], off offset:256
	v_cvt_f32_f16_sdwa v139, v163 dst_sel:DWORD dst_unused:UNUSED_PAD src0_sel:WORD_1
	v_add_co_u32_e32 v132, vcc, s6, v2
	s_mov_b32 s6, 0xa0000
	v_fma_f32 v138, v94, v126, v138
	v_fma_f32 v139, v95, v127, v139
	v_fma_f32 v94, v92, v124, v136
	v_fma_f32 v95, v93, v125, v137
	v_addc_co_u32_e32 v133, vcc, 0, v3, vcc
	v_cvt_pk_f16_f32 v92, v96, v97
	v_cvt_pk_f16_f32 v93, v98, v99
	v_cvt_pk_f16_f32 v94, v94, v95
	v_cvt_pk_f16_f32 v95, v138, v139
	s_nop 0
	global_store_dwordx4 v[170:171], v[92:95], off
	s_nop 1
	s_waitcnt vmcnt(15)
	v_cvt_f32_f16_e32 v92, v156
	v_cvt_f32_f16_sdwa v93, v156 dst_sel:DWORD dst_unused:UNUSED_PAD src0_sel:WORD_1
	v_cvt_f32_f16_e32 v94, v157
	v_cvt_f32_f16_sdwa v95, v157 dst_sel:DWORD dst_unused:UNUSED_PAD src0_sel:WORD_1
	v_fma_f32 v88, v88, v120, v92
	v_fma_f32 v89, v89, v121, v93
	v_cvt_f32_f16_e32 v92, v158
	v_fma_f32 v90, v90, v122, v94
	v_fma_f32 v91, v91, v123, v95
	v_cvt_f32_f16_sdwa v93, v158 dst_sel:DWORD dst_unused:UNUSED_PAD src0_sel:WORD_1
	v_cvt_f32_f16_e32 v94, v159
	v_cvt_f32_f16_sdwa v95, v159 dst_sel:DWORD dst_unused:UNUSED_PAD src0_sel:WORD_1
	v_fma_f32 v94, v86, v114, v94
	v_fma_f32 v95, v87, v115, v95
	v_fma_f32 v86, v84, v112, v92
	v_fma_f32 v87, v85, v113, v93
	v_cvt_pk_f16_f32 v84, v88, v89
	v_cvt_pk_f16_f32 v85, v90, v91
	v_cvt_pk_f16_f32 v86, v86, v87
	v_cvt_pk_f16_f32 v87, v94, v95
	global_store_dwordx4 v[170:171], v[84:87], off offset:256
	s_waitcnt vmcnt(13)
; #define ER_LOAD(dst, ai, mp) do { _Pragma("unroll") for (int mm = 0; mm < 2; ++mm) _Pragma("unroll") for (int bj = 0; bj < 2; ++bj) \
;             dst[mm][bj] = *(const u32x4*)(xb + (size_t)((ai) * HALF + (2 * (mp) + mm) * 16) * 2048 + bj * HALF); } while (0)
;     __device__ __forceinline__ void operator()(const f32x4 (&acc)[2][2][4][2], const Unit& u, int wr, int wc, int fr, int fq) const {
;     ...
;         ER_LOAD(xa, 0, 0); ER_LOAD(xc, 0, 1);
;         ER_STORE(xa, 0, 0); ER_LOAD(xa, 1, 0);
;         ER_STORE(xc, 0, 1); ER_LOAD(xc, 1, 1);
;         ER_STORE(xa, 1, 0); ER_STORE(xc, 1, 1);
	v_cvt_f32_f16_e32 v88, v213
	v_cvt_f32_f16_e32 v84, v152
	v_cvt_f32_f16_sdwa v85, v152 dst_sel:DWORD dst_unused:UNUSED_PAD src0_sel:WORD_1
	v_cvt_f32_f16_e32 v86, v153
	v_cvt_f32_f16_sdwa v87, v153 dst_sel:DWORD dst_unused:UNUSED_PAD src0_sel:WORD_1
	v_cvt_f32_f16_sdwa v89, v213 dst_sel:DWORD dst_unused:UNUSED_PAD src0_sel:WORD_1
	v_fma_f32 v80, v80, v128, v84
	v_fma_f32 v81, v81, v129, v85
	v_cvt_f32_f16_e32 v84, v154
	v_fma_f32 v82, v82, v130, v86
	v_fma_f32 v83, v83, v131, v87
	v_cvt_f32_f16_sdwa v85, v154 dst_sel:DWORD dst_unused:UNUSED_PAD src0_sel:WORD_1
	v_cvt_f32_f16_e32 v86, v155
	v_cvt_f32_f16_sdwa v87, v155 dst_sel:DWORD dst_unused:UNUSED_PAD src0_sel:WORD_1
	v_fma_f32 v66, v66, v130, v88
	v_fma_f32 v67, v67, v131, v89
	v_cvt_f32_f16_e32 v88, v215
	v_cvt_f32_f16_sdwa v89, v215 dst_sel:DWORD dst_unused:UNUSED_PAD src0_sel:WORD_1
	v_fma_f32 v86, v78, v126, v86
	v_fma_f32 v87, v79, v127, v87
	v_fma_f32 v78, v76, v124, v84
	v_fma_f32 v79, v77, v125, v85
	v_cvt_pk_f16_f32 v76, v80, v81
	v_cvt_pk_f16_f32 v77, v82, v83
	v_cvt_pk_f16_f32 v78, v78, v79
	v_cvt_pk_f16_f32 v79, v86, v87
	global_store_dwordx4 v[168:169], v[76:79], off
	v_add_co_u32_e32 v84, vcc, s6, v2
	s_nop 0
	v_cvt_f32_f16_e32 v76, v148
	v_cvt_f32_f16_sdwa v77, v148 dst_sel:DWORD dst_unused:UNUSED_PAD src0_sel:WORD_1
	v_cvt_f32_f16_e32 v78, v149
	v_cvt_f32_f16_sdwa v79, v149 dst_sel:DWORD dst_unused:UNUSED_PAD src0_sel:WORD_1
	v_addc_co_u32_e32 v85, vcc, 0, v3, vcc
	v_fma_f32 v72, v72, v120, v76
	v_fma_f32 v73, v73, v121, v77
	v_fma_f32 v74, v74, v122, v78
	v_fma_f32 v75, v75, v123, v79
	v_cvt_f32_f16_e32 v76, v150
	v_cvt_f32_f16_sdwa v77, v150 dst_sel:DWORD dst_unused:UNUSED_PAD src0_sel:WORD_1
	v_cvt_f32_f16_e32 v78, v151
	v_cvt_f32_f16_sdwa v79, v151 dst_sel:DWORD dst_unused:UNUSED_PAD src0_sel:WORD_1
	s_mov_b32 s6, 0xb0000
	v_add_co_u32_e32 v2, vcc, s6, v2
	v_fma_f32 v78, v70, v114, v78
	v_fma_f32 v79, v71, v115, v79
	v_fma_f32 v70, v68, v112, v76
	v_fma_f32 v71, v69, v113, v77
	v_cvt_pk_f16_f32 v68, v72, v73
	v_cvt_pk_f16_f32 v69, v74, v75
	v_cvt_pk_f16_f32 v70, v70, v71
	v_cvt_pk_f16_f32 v71, v78, v79
	global_store_dwordx4 v[168:169], v[68:71], off offset:256
	v_addc_co_u32_e32 v3, vcc, 0, v3, vcc
	v_cvt_f32_f16_e32 v86, v212
	v_cvt_f32_f16_sdwa v87, v212 dst_sel:DWORD dst_unused:UNUSED_PAD src0_sel:WORD_1
	v_fma_f32 v88, v62, v126, v88
	v_fma_f32 v89, v63, v127, v89
	s_and_b64 vcc, s[16:17], exec
	v_fma_f32 v64, v64, v128, v86
	v_fma_f32 v65, v65, v129, v87
	v_cvt_f32_f16_e32 v86, v214
	v_cvt_f32_f16_sdwa v87, v214 dst_sel:DWORD dst_unused:UNUSED_PAD src0_sel:WORD_1
	v_fma_f32 v62, v60, v124, v86
	v_fma_f32 v63, v61, v125, v87
	v_cvt_pk_f16_f32 v60, v64, v65
	v_cvt_pk_f16_f32 v61, v66, v67
	v_cvt_pk_f16_f32 v62, v62, v63
	v_cvt_pk_f16_f32 v63, v88, v89
	global_store_dwordx4 v[134:135], v[60:63], off
	s_nop 1
	s_waitcnt vmcnt(15)
	v_cvt_f32_f16_e32 v60, v216
	v_cvt_f32_f16_sdwa v61, v216 dst_sel:DWORD dst_unused:UNUSED_PAD src0_sel:WORD_1
	v_cvt_f32_f16_e32 v62, v217
	v_cvt_f32_f16_sdwa v63, v217 dst_sel:DWORD dst_unused:UNUSED_PAD src0_sel:WORD_1
	v_fma_f32 v56, v56, v120, v60
	v_fma_f32 v57, v57, v121, v61
	v_cvt_f32_f16_e32 v60, v218
	v_fma_f32 v58, v58, v122, v62
	v_fma_f32 v59, v59, v123, v63
	v_cvt_f32_f16_sdwa v61, v218 dst_sel:DWORD dst_unused:UNUSED_PAD src0_sel:WORD_1
	v_cvt_f32_f16_e32 v62, v219
	v_cvt_f32_f16_sdwa v63, v219 dst_sel:DWORD dst_unused:UNUSED_PAD src0_sel:WORD_1
	v_fma_f32 v62, v54, v114, v62
	v_fma_f32 v63, v55, v115, v63
	v_fma_f32 v54, v52, v112, v60
	v_fma_f32 v55, v53, v113, v61
	v_cvt_pk_f16_f32 v52, v56, v57
	v_cvt_pk_f16_f32 v53, v58, v59
	v_cvt_pk_f16_f32 v54, v54, v55
	v_cvt_pk_f16_f32 v55, v62, v63
	global_store_dwordx4 v[134:135], v[52:55], off offset:256
	s_nop 1
	s_waitcnt vmcnt(15)
	v_cvt_f32_f16_e32 v52, v220
	v_cvt_f32_f16_sdwa v53, v220 dst_sel:DWORD dst_unused:UNUSED_PAD src0_sel:WORD_1
	v_cvt_f32_f16_e32 v54, v221
	v_cvt_f32_f16_sdwa v55, v221 dst_sel:DWORD dst_unused:UNUSED_PAD src0_sel:WORD_1
	v_fma_f32 v48, v48, v128, v52
	v_fma_f32 v49, v49, v129, v53
	v_cvt_f32_f16_e32 v52, v222
	v_fma_f32 v50, v50, v130, v54
	v_fma_f32 v51, v51, v131, v55
	v_cvt_f32_f16_sdwa v53, v222 dst_sel:DWORD dst_unused:UNUSED_PAD src0_sel:WORD_1
	v_cvt_f32_f16_e32 v54, v223
	v_cvt_f32_f16_sdwa v55, v223 dst_sel:DWORD dst_unused:UNUSED_PAD src0_sel:WORD_1
	v_fma_f32 v54, v46, v126, v54
	v_fma_f32 v55, v47, v127, v55
	v_fma_f32 v46, v44, v124, v52
	v_fma_f32 v47, v45, v125, v53
	v_cvt_pk_f16_f32 v44, v48, v49
	v_cvt_pk_f16_f32 v45, v50, v51
	v_cvt_pk_f16_f32 v46, v46, v47
	v_cvt_pk_f16_f32 v47, v54, v55
	global_store_dwordx4 v[132:133], v[44:47], off
	s_nop 1
	s_waitcnt vmcnt(15)
	v_cvt_f32_f16_e32 v44, v224
	v_cvt_f32_f16_sdwa v45, v224 dst_sel:DWORD dst_unused:UNUSED_PAD src0_sel:WORD_1
	v_cvt_f32_f16_e32 v46, v225
	v_cvt_f32_f16_sdwa v47, v225 dst_sel:DWORD dst_unused:UNUSED_PAD src0_sel:WORD_1
	v_fma_f32 v40, v40, v120, v44
	v_fma_f32 v41, v41, v121, v45
	v_cvt_f32_f16_e32 v44, v226
	v_fma_f32 v42, v42, v122, v46
	v_fma_f32 v43, v43, v123, v47
	v_cvt_f32_f16_sdwa v45, v226 dst_sel:DWORD dst_unused:UNUSED_PAD src0_sel:WORD_1
	v_cvt_f32_f16_e32 v46, v227
	v_cvt_f32_f16_sdwa v47, v227 dst_sel:DWORD dst_unused:UNUSED_PAD src0_sel:WORD_1
	v_fma_f32 v46, v38, v114, v46
	v_fma_f32 v47, v39, v115, v47
	v_fma_f32 v38, v36, v112, v44
	v_fma_f32 v39, v37, v113, v45
	v_cvt_pk_f16_f32 v36, v40, v41
	v_cvt_pk_f16_f32 v37, v42, v43
	v_cvt_pk_f16_f32 v38, v38, v39
	v_cvt_pk_f16_f32 v39, v46, v47
	global_store_dwordx4 v[132:133], v[36:39], off offset:256
	s_nop 0
	s_waitcnt vmcnt(15)
; #define ER_LOAD(dst, ai, mp) do { _Pragma("unroll") for (int mm = 0; mm < 2; ++mm) _Pragma("unroll") for (int bj = 0; bj < 2; ++bj) \
;             dst[mm][bj] = *(const u32x4*)(xb + (size_t)((ai) * HALF + (2 * (mp) + mm) * 16) * 2048 + bj * HALF); } while (0)
; #define PG8_BAR __builtin_amdgcn_s_barrier()
;     __device__ __forceinline__ void operator()(const f32x4 (&acc)[2][2][4][2], const Unit& u, int wr, int wc, int fr, int fq) const {
;     ...
;         ER_LOAD(xa, 0, 0); ER_LOAD(xc, 0, 1);
;         ER_STORE(xa, 0, 0); ER_LOAD(xa, 1, 0);
;         ER_STORE(xc, 0, 1); ER_LOAD(xc, 1, 1);
;         ER_STORE(xa, 1, 0); ER_STORE(xc, 1, 1);
; template <class Epi, class Sched, bool ALIGN_EPI = false, bool SP2 = false>
; __device__ __forceinline__ void gemm_phase(PG8_LAS unsigned char* lds, const Gemm g, const Sched& S, const Epi& E) {
;     ...
;         cur = nxt; cA = nA; cB = nB; ++ui;
;         if constexpr (ALIGN_EPI) { if (wr == 1) PG8_BAR; }
;         if constexpr (DRO) {
;             const char* a1 = cA + kstep; const char* a2 = cA + 2 * kstep; const char* b2 = cB + 2 * kstep; const char* a3 = a2 + kstep; const char* b3 = b2 + kstep;
;             PG8_TRIP(false, asm volatile("s_waitcnt vmcnt(%0)" :: "n"(8 + Epi::NVM) : "memory"));
;         }
	v_cvt_f32_f16_e32 v36, v228
	v_cvt_f32_f16_sdwa v37, v228 dst_sel:DWORD dst_unused:UNUSED_PAD src0_sel:WORD_1
	v_cvt_f32_f16_e32 v38, v229
	v_cvt_f32_f16_sdwa v39, v229 dst_sel:DWORD dst_unused:UNUSED_PAD src0_sel:WORD_1
	v_fma_f32 v32, v32, v128, v36
	v_fma_f32 v33, v33, v129, v37
	v_cvt_f32_f16_e32 v36, v230
	v_fma_f32 v34, v34, v130, v38
	v_fma_f32 v35, v35, v131, v39
	v_cvt_f32_f16_sdwa v37, v230 dst_sel:DWORD dst_unused:UNUSED_PAD src0_sel:WORD_1
	v_cvt_f32_f16_e32 v38, v231
	v_cvt_f32_f16_sdwa v39, v231 dst_sel:DWORD dst_unused:UNUSED_PAD src0_sel:WORD_1
	v_fma_f32 v38, v30, v126, v38
	v_fma_f32 v39, v31, v127, v39
	v_fma_f32 v30, v28, v124, v36
	v_fma_f32 v31, v29, v125, v37
	v_cvt_pk_f16_f32 v28, v32, v33
	v_cvt_pk_f16_f32 v29, v34, v35
	v_cvt_pk_f16_f32 v30, v30, v31
	v_cvt_pk_f16_f32 v31, v38, v39
	global_store_dwordx4 v[84:85], v[28:31], off
	s_nop 1
	s_waitcnt vmcnt(15)
	v_cvt_f32_f16_e32 v28, v232
	v_cvt_f32_f16_sdwa v29, v232 dst_sel:DWORD dst_unused:UNUSED_PAD src0_sel:WORD_1
	v_cvt_f32_f16_e32 v30, v233
	v_cvt_f32_f16_sdwa v31, v233 dst_sel:DWORD dst_unused:UNUSED_PAD src0_sel:WORD_1
	v_fma_f32 v24, v24, v120, v28
	v_fma_f32 v25, v25, v121, v29
	v_cvt_f32_f16_e32 v28, v234
	v_fma_f32 v26, v26, v122, v30
	v_fma_f32 v27, v27, v123, v31
	v_cvt_f32_f16_sdwa v29, v234 dst_sel:DWORD dst_unused:UNUSED_PAD src0_sel:WORD_1
	v_cvt_f32_f16_e32 v30, v235
	v_cvt_f32_f16_sdwa v31, v235 dst_sel:DWORD dst_unused:UNUSED_PAD src0_sel:WORD_1
	v_fma_f32 v30, v22, v114, v30
	v_fma_f32 v31, v23, v115, v31
	v_fma_f32 v22, v20, v112, v28
	v_fma_f32 v23, v21, v113, v29
	v_cvt_pk_f16_f32 v20, v24, v25
	v_cvt_pk_f16_f32 v21, v26, v27
	v_cvt_pk_f16_f32 v22, v22, v23
	v_cvt_pk_f16_f32 v23, v30, v31
	global_store_dwordx4 v[84:85], v[20:23], off offset:256
	s_nop 1
	s_waitcnt vmcnt(15)
	v_cvt_f32_f16_e32 v20, v236
	v_cvt_f32_f16_sdwa v21, v236 dst_sel:DWORD dst_unused:UNUSED_PAD src0_sel:WORD_1
	v_cvt_f32_f16_e32 v22, v237
	v_cvt_f32_f16_sdwa v23, v237 dst_sel:DWORD dst_unused:UNUSED_PAD src0_sel:WORD_1
	v_fma_f32 v16, v16, v128, v20
	v_fma_f32 v17, v17, v129, v21
	v_cvt_f32_f16_e32 v20, v238
	v_fma_f32 v18, v18, v130, v22
	v_fma_f32 v19, v19, v131, v23
	v_cvt_f32_f16_sdwa v21, v238 dst_sel:DWORD dst_unused:UNUSED_PAD src0_sel:WORD_1
	v_cvt_f32_f16_e32 v22, v239
	v_cvt_f32_f16_sdwa v23, v239 dst_sel:DWORD dst_unused:UNUSED_PAD src0_sel:WORD_1
	v_fma_f32 v22, v14, v126, v22
	v_fma_f32 v23, v15, v127, v23
	v_fma_f32 v14, v12, v124, v20
	v_fma_f32 v15, v13, v125, v21
	v_cvt_pk_f16_f32 v12, v16, v17
	v_cvt_pk_f16_f32 v13, v18, v19
	v_cvt_pk_f16_f32 v14, v14, v15
	v_cvt_pk_f16_f32 v15, v22, v23
	global_store_dwordx4 v[2:3], v[12:15], off
	s_nop 1
	s_waitcnt vmcnt(15)
	v_cvt_f32_f16_e32 v12, v240
	v_cvt_f32_f16_sdwa v13, v240 dst_sel:DWORD dst_unused:UNUSED_PAD src0_sel:WORD_1
	v_cvt_f32_f16_e32 v14, v241
	v_cvt_f32_f16_sdwa v15, v241 dst_sel:DWORD dst_unused:UNUSED_PAD src0_sel:WORD_1
	v_fma_f32 v8, v8, v120, v12
	v_fma_f32 v9, v9, v121, v13
	v_cvt_f32_f16_e32 v12, v242
	v_fma_f32 v10, v10, v122, v14
	v_fma_f32 v11, v11, v123, v15
	v_cvt_f32_f16_sdwa v13, v242 dst_sel:DWORD dst_unused:UNUSED_PAD src0_sel:WORD_1
	v_cvt_f32_f16_e32 v14, v243
	v_cvt_f32_f16_sdwa v15, v243 dst_sel:DWORD dst_unused:UNUSED_PAD src0_sel:WORD_1
	v_fma_f32 v14, v6, v114, v14
	v_fma_f32 v15, v7, v115, v15
	v_fma_f32 v6, v4, v112, v12
	v_fma_f32 v7, v5, v113, v13
	v_cvt_pk_f16_f32 v4, v8, v9
	v_cvt_pk_f16_f32 v5, v10, v11
	v_cvt_pk_f16_f32 v6, v6, v7
	v_cvt_pk_f16_f32 v7, v14, v15
	global_store_dwordx4 v[2:3], v[4:7], off offset:256
	s_cbranch_vccz .LBB0_919
	ds_read_b128 v[2:5], v0
	ds_read_b128 v[6:9], v0 offset:1024
	ds_read_b128 v[10:13], v0 offset:2048
	ds_read_b128 v[14:17], v0 offset:3072
	ds_read_b128 v[18:21], v188
	ds_read_b128 v[22:25], v188 offset:1024
	ds_read_b128 v[26:29], v188 offset:2048
	ds_read_b128 v[30:33], v188 offset:3072
	s_add_u32 s18, s12, 0x100
	s_addc_u32 s19, s13, 0
	s_add_u32 s16, s12, 0x180
	s_addc_u32 s17, s13, 0
	s_add_u32 s6, s14, 0x100
	s_addc_u32 s7, s15, 0
	ds_read_b128 v[34:37], v187
	ds_read_b128 v[38:41], v187 offset:1024
	ds_read_b128 v[42:45], v187 offset:2048
	ds_read_b128 v[46:49], v187 offset:3072
	ds_read_b128 v[50:53], v187 offset:4096
	ds_read_b128 v[54:57], v187 offset:5120
	ds_read_b128 v[58:61], v187 offset:6144
	ds_read_b128 v[62:65], v187 offset:7168
	s_waitcnt vmcnt(44)
	s_waitcnt lgkmcnt(0)
	s_barrier
	s_setprio 1
	s_waitcnt lgkmcnt(0)
	v_mfma_f32_16x16x32_bf16 v[90:93], v[2:5], v[58:61], 0
	v_mfma_f32_16x16x32_bf16 v[66:69], v[2:5], v[34:37], 0
	v_mfma_f32_16x16x32_bf16 v[70:73], v[10:13], v[34:37], 0
	v_mfma_f32_16x16x32_bf16 v[74:77], v[2:5], v[42:45], 0
	v_mfma_f32_16x16x32_bf16 v[78:81], v[10:13], v[42:45], 0
	v_mfma_f32_16x16x32_bf16 v[82:85], v[2:5], v[50:53], 0
	v_mfma_f32_16x16x32_bf16 v[86:89], v[10:13], v[50:53], 0
	v_mfma_f32_16x16x32_bf16 v[100:103], v[6:9], v[62:65], v[90:93]
	v_mfma_f32_16x16x32_bf16 v[90:93], v[10:13], v[58:61], 0
	v_mfma_f32_16x16x32_bf16 v[66:69], v[6:9], v[38:41], v[66:69]
	v_mfma_f32_16x16x32_bf16 v[70:73], v[14:17], v[38:41], v[70:73]
	v_mfma_f32_16x16x32_bf16 v[74:77], v[6:9], v[46:49], v[74:77]
	v_mfma_f32_16x16x32_bf16 v[78:81], v[14:17], v[46:49], v[78:81]
	v_mfma_f32_16x16x32_bf16 v[82:85], v[6:9], v[54:57], v[82:85]
	v_mfma_f32_16x16x32_bf16 v[86:89], v[14:17], v[54:57], v[86:89]
	v_mfma_f32_16x16x32_bf16 v[104:107], v[14:17], v[62:65], v[90:93]
	s_setprio 0
	s_setprio 1
	v_mfma_f32_16x16x32_bf16 v[90:93], v[18:21], v[34:37], 0
	v_mfma_f32_16x16x32_bf16 v[34:37], v[26:29], v[34:37], 0
	v_mfma_f32_16x16x32_bf16 v[112:115], v[22:25], v[38:41], v[90:93]
	v_mfma_f32_16x16x32_bf16 v[34:37], v[30:33], v[38:41], v[34:37]
	v_mfma_f32_16x16x32_bf16 v[38:41], v[18:21], v[42:45], 0
	v_mfma_f32_16x16x32_bf16 v[42:45], v[26:29], v[42:45], 0
	v_mfma_f32_16x16x32_bf16 v[38:41], v[22:25], v[46:49], v[38:41]
	v_mfma_f32_16x16x32_bf16 v[42:45], v[30:33], v[46:49], v[42:45]
	v_mfma_f32_16x16x32_bf16 v[46:49], v[18:21], v[50:53], 0
	v_mfma_f32_16x16x32_bf16 v[50:53], v[26:29], v[50:53], 0
	v_mfma_f32_16x16x32_bf16 v[46:49], v[22:25], v[54:57], v[46:49]
	v_mfma_f32_16x16x32_bf16 v[50:53], v[30:33], v[54:57], v[50:53]
	v_mfma_f32_16x16x32_bf16 v[54:57], v[18:21], v[58:61], 0
	v_mfma_f32_16x16x32_bf16 v[58:61], v[26:29], v[58:61], 0
	v_mfma_f32_16x16x32_bf16 v[54:57], v[22:25], v[62:65], v[54:57]
	v_mfma_f32_16x16x32_bf16 v[58:61], v[30:33], v[62:65], v[58:61]
	s_setprio 0
	s_barrier
	ds_read_b128 v[62:65], v187 offset:16384
	ds_read_b128 v[90:93], v187 offset:17408
	ds_read_b128 v[94:97], v187 offset:18432
	ds_read_b128 v[108:111], v187 offset:19456
	ds_read_b128 v[116:119], v187 offset:20480
	ds_read_b128 v[120:123], v187 offset:21504
	ds_read_b128 v[124:127], v187 offset:22528
	ds_read_b128 v[128:131], v187 offset:23552
	s_mov_b32 m0, s28
	s_nop 0
	global_load_lds_dwordx4 v175, s[6:7]
	s_nop 0
	s_mov_b32 m0, s29
	s_nop 0
	global_load_lds_dwordx4 v177, s[6:7]
	s_add_u32 s6, s14, 0x80100
	s_addc_u32 s7, s15, 0
	s_mov_b32 m0, s30
	s_nop 0
	global_load_lds_dwordx4 v175, s[6:7]
	s_nop 0
	s_mov_b32 m0, s31
	s_nop 0
	global_load_lds_dwordx4 v177, s[6:7]
	s_nop 0
	s_mov_b32 m0, s27
	s_nop 0
	global_load_lds_dwordx4 v174, s[18:19]
	s_nop 0
	s_mov_b32 m0, s35
	s_nop 0
	global_load_lds_dwordx4 v176, s[18:19]
	s_waitcnt vmcnt(44)
	s_waitcnt lgkmcnt(0)
	s_barrier
	s_setprio 1
	s_waitcnt lgkmcnt(0)
	v_mfma_f32_16x16x32_bf16 v[132:135], v[2:5], v[62:65], 0
	v_mfma_f32_16x16x32_bf16 v[148:151], v[6:9], v[90:93], v[132:135]
	v_mfma_f32_16x16x32_bf16 v[132:135], v[10:13], v[62:65], 0
	v_mfma_f32_16x16x32_bf16 v[152:155], v[14:17], v[90:93], v[132:135]
	v_mfma_f32_16x16x32_bf16 v[132:135], v[2:5], v[94:97], 0
	v_mfma_f32_16x16x32_bf16 v[156:159], v[6:9], v[108:111], v[132:135]
	v_mfma_f32_16x16x32_bf16 v[132:135], v[10:13], v[94:97], 0
	v_mfma_f32_16x16x32_bf16 v[160:163], v[14:17], v[108:111], v[132:135]
	v_mfma_f32_16x16x32_bf16 v[132:135], v[2:5], v[116:119], 0
	v_mfma_f32_16x16x32_bf16 v[2:5], v[2:5], v[124:127], 0
	v_mfma_f32_16x16x32_bf16 v[164:167], v[6:9], v[120:123], v[132:135]
	v_mfma_f32_16x16x32_bf16 v[2:5], v[6:9], v[128:131], v[2:5]
	v_mfma_f32_16x16x32_bf16 v[6:9], v[10:13], v[124:127], 0
	v_mfma_f32_16x16x32_bf16 v[132:135], v[10:13], v[116:119], 0
	v_mfma_f32_16x16x32_bf16 v[6:9], v[14:17], v[128:131], v[6:9]
	v_mfma_f32_16x16x32_bf16 v[168:171], v[14:17], v[120:123], v[132:135]
	s_setprio 0
	s_setprio 1
	v_mfma_f32_16x16x32_bf16 v[10:13], v[18:21], v[62:65], 0
	v_mfma_f32_16x16x32_bf16 v[178:181], v[22:25], v[90:93], v[10:13]
	v_mfma_f32_16x16x32_bf16 v[10:13], v[26:29], v[62:65], 0
	v_mfma_f32_16x16x32_bf16 v[192:195], v[30:33], v[90:93], v[10:13]
	v_mfma_f32_16x16x32_bf16 v[10:13], v[18:21], v[94:97], 0
	v_mfma_f32_16x16x32_bf16 v[196:199], v[22:25], v[108:111], v[10:13]
	v_mfma_f32_16x16x32_bf16 v[10:13], v[26:29], v[94:97], 0
	v_mfma_f32_16x16x32_bf16 v[200:203], v[30:33], v[108:111], v[10:13]
	v_mfma_f32_16x16x32_bf16 v[10:13], v[18:21], v[116:119], 0
	v_mfma_f32_16x16x32_bf16 v[204:207], v[22:25], v[120:123], v[10:13]
	v_mfma_f32_16x16x32_bf16 v[10:13], v[26:29], v[116:119], 0
	v_mfma_f32_16x16x32_bf16 v[120:123], v[30:33], v[120:123], v[10:13]
	v_mfma_f32_16x16x32_bf16 v[10:13], v[18:21], v[124:127], 0
	v_mfma_f32_16x16x32_bf16 v[208:211], v[22:25], v[128:131], v[10:13]
	v_mfma_f32_16x16x32_bf16 v[10:13], v[26:29], v[124:127], 0
	v_mfma_f32_16x16x32_bf16 v[124:127], v[30:33], v[128:131], v[10:13]
	s_setprio 0
	s_barrier
	s_nop 4
	ds_read_b128 v[10:13], v189
	ds_read_b128 v[14:17], v189 offset:1024
	ds_read_b128 v[20:23], v189 offset:2048
	ds_read_b128 v[24:27], v189 offset:3072
	ds_read_b128 v[128:131], v190
	ds_read_b128 v[212:215], v190 offset:1024
	ds_read_b128 v[216:219], v190 offset:2048
	ds_read_b128 v[188:191], v190 offset:3072
	ds_read_b128 v[28:31], v187 offset:32768
	ds_read_b128 v[62:65], v187 offset:33792
	ds_read_b128 v[220:223], v187 offset:34816
	ds_read_b128 v[224:227], v187 offset:35840
	ds_read_b128 v[228:231], v187 offset:36864
	ds_read_b128 v[232:235], v187 offset:37888
	ds_read_b128 v[236:239], v187 offset:38912
	ds_read_b128 v[240:243], v187 offset:39936
	s_add_u32 s6, s12, 0x80100
	s_addc_u32 s7, s13, 0
	s_mov_b32 m0, s36
	s_nop 0
	global_load_lds_dwordx4 v174, s[6:7]
	s_nop 0
	s_mov_b32 m0, s37
	s_nop 0
	global_load_lds_dwordx4 v176, s[6:7]
	s_waitcnt vmcnt(44)
	s_waitcnt lgkmcnt(0)
	s_barrier
	s_setprio 1
	s_waitcnt lgkmcnt(0)
	v_mfma_f32_16x16x32_bf16 v[66:69], v[10:13], v[28:31], v[66:69]
	v_mfma_f32_16x16x32_bf16 v[144:147], v[14:17], v[62:65], v[66:69]
	v_mfma_f32_16x16x32_bf16 v[66:69], v[20:23], v[28:31], v[70:73]
	v_mfma_f32_16x16x32_bf16 v[140:143], v[24:27], v[62:65], v[66:69]
	v_mfma_f32_16x16x32_bf16 v[66:69], v[10:13], v[220:223], v[74:77]
	v_mfma_f32_16x16x32_bf16 v[116:119], v[14:17], v[224:227], v[66:69]
	v_mfma_f32_16x16x32_bf16 v[66:69], v[20:23], v[220:223], v[78:81]
	v_mfma_f32_16x16x32_bf16 v[108:111], v[24:27], v[224:227], v[66:69]
	v_mfma_f32_16x16x32_bf16 v[66:69], v[10:13], v[228:231], v[82:85]
	v_mfma_f32_16x16x32_bf16 v[96:99], v[14:17], v[232:235], v[66:69]
	v_mfma_f32_16x16x32_bf16 v[66:69], v[20:23], v[228:231], v[86:89]
	v_mfma_f32_16x16x32_bf16 v[92:95], v[24:27], v[232:235], v[66:69]
	v_mfma_f32_16x16x32_bf16 v[66:69], v[10:13], v[236:239], v[100:103]
	v_mfma_f32_16x16x32_bf16 v[80:83], v[14:17], v[240:243], v[66:69]
	v_mfma_f32_16x16x32_bf16 v[66:69], v[20:23], v[236:239], v[104:107]
	v_mfma_f32_16x16x32_bf16 v[76:79], v[24:27], v[240:243], v[66:69]
	s_setprio 0
	s_setprio 1
	v_mfma_f32_16x16x32_bf16 v[66:69], v[128:131], v[28:31], v[112:115]
	v_mfma_f32_16x16x32_bf16 v[28:31], v[216:219], v[28:31], v[34:37]
	v_mfma_f32_16x16x32_bf16 v[132:135], v[188:191], v[62:65], v[28:31]
	v_mfma_f32_16x16x32_bf16 v[28:31], v[128:131], v[220:223], v[38:41]
	v_mfma_f32_16x16x32_bf16 v[104:107], v[212:215], v[224:227], v[28:31]
	v_mfma_f32_16x16x32_bf16 v[28:31], v[216:219], v[220:223], v[42:45]
	v_mfma_f32_16x16x32_bf16 v[100:103], v[188:191], v[224:227], v[28:31]
	v_mfma_f32_16x16x32_bf16 v[28:31], v[128:131], v[228:231], v[46:49]
	v_mfma_f32_16x16x32_bf16 v[88:91], v[212:215], v[232:235], v[28:31]
	v_mfma_f32_16x16x32_bf16 v[28:31], v[216:219], v[228:231], v[50:53]
	v_mfma_f32_16x16x32_bf16 v[84:87], v[188:191], v[232:235], v[28:31]
	v_mfma_f32_16x16x32_bf16 v[28:31], v[128:131], v[236:239], v[54:57]
	v_mfma_f32_16x16x32_bf16 v[72:75], v[212:215], v[240:243], v[28:31]
	v_mfma_f32_16x16x32_bf16 v[28:31], v[216:219], v[236:239], v[58:61]
	v_mfma_f32_16x16x32_bf16 v[136:139], v[212:215], v[62:65], v[66:69]
	v_mfma_f32_16x16x32_bf16 v[68:71], v[188:191], v[240:243], v[28:31]
	s_setprio 0
	s_barrier
	ds_read_b128 v[36:39], v187 offset:49152
	ds_read_b128 v[40:43], v187 offset:50176
	ds_read_b128 v[112:115], v187 offset:51200
	ds_read_b128 v[220:223], v187 offset:52224
	ds_read_b128 v[224:227], v187 offset:53248
	ds_read_b128 v[228:231], v187 offset:54272
	ds_read_b128 v[232:235], v187 offset:55296
	ds_read_b128 v[236:239], v187 offset:56320
	s_add_u32 s6, s14, 0x180
	s_addc_u32 s7, s15, 0
	s_mov_b32 m0, s44
	s_nop 0
	global_load_lds_dwordx4 v175, s[6:7]
	s_nop 0
	s_mov_b32 m0, s48
	s_nop 0
	global_load_lds_dwordx4 v177, s[6:7]
	s_add_u32 s6, s14, 0x80180
	s_addc_u32 s7, s15, 0
	s_mov_b32 m0, s52
	s_nop 0
	global_load_lds_dwordx4 v175, s[6:7]
	s_nop 0
	s_mov_b32 m0, s53
	s_nop 0
	global_load_lds_dwordx4 v177, s[6:7]
	s_nop 0
	s_mov_b32 m0, s49
	s_nop 0
	global_load_lds_dwordx4 v174, s[16:17]
	s_nop 0
	s_mov_b32 m0, s51
	s_nop 0
	global_load_lds_dwordx4 v176, s[16:17]
	s_waitcnt vmcnt(8)
	s_waitcnt lgkmcnt(0)
	s_barrier
	s_setprio 1
	s_waitcnt lgkmcnt(0)
	v_mfma_f32_16x16x32_bf16 v[28:31], v[10:13], v[36:39], v[148:151]
	v_mfma_f32_16x16x32_bf16 v[64:67], v[14:17], v[40:43], v[28:31]
	v_mfma_f32_16x16x32_bf16 v[28:31], v[20:23], v[36:39], v[152:155]
	v_mfma_f32_16x16x32_bf16 v[60:63], v[24:27], v[40:43], v[28:31]
	v_mfma_f32_16x16x32_bf16 v[28:31], v[10:13], v[112:115], v[156:159]
	v_mfma_f32_16x16x32_bf16 v[48:51], v[14:17], v[220:223], v[28:31]
	v_mfma_f32_16x16x32_bf16 v[28:31], v[20:23], v[112:115], v[160:163]
	v_mfma_f32_16x16x32_bf16 v[44:47], v[24:27], v[220:223], v[28:31]
	v_mfma_f32_16x16x32_bf16 v[28:31], v[10:13], v[224:227], v[164:167]
	v_mfma_f32_16x16x32_bf16 v[2:5], v[10:13], v[232:235], v[2:5]
	v_mfma_f32_16x16x32_bf16 v[32:35], v[14:17], v[228:231], v[28:31]
	v_mfma_f32_16x16x32_bf16 v[28:31], v[20:23], v[224:227], v[168:171]
	v_mfma_f32_16x16x32_bf16 v[16:19], v[14:17], v[236:239], v[2:5]
	v_mfma_f32_16x16x32_bf16 v[2:5], v[20:23], v[232:235], v[6:9]
	v_mfma_f32_16x16x32_bf16 v[28:31], v[24:27], v[228:231], v[28:31]
	v_mfma_f32_16x16x32_bf16 v[12:15], v[24:27], v[236:239], v[2:5]
	s_setprio 0
	s_setprio 1
	v_mfma_f32_16x16x32_bf16 v[2:5], v[128:131], v[36:39], v[178:181]
	v_mfma_f32_16x16x32_bf16 v[56:59], v[212:215], v[40:43], v[2:5]
	v_mfma_f32_16x16x32_bf16 v[2:5], v[216:219], v[36:39], v[192:195]
	v_mfma_f32_16x16x32_bf16 v[52:55], v[188:191], v[40:43], v[2:5]
	v_mfma_f32_16x16x32_bf16 v[2:5], v[128:131], v[112:115], v[196:199]
	v_mfma_f32_16x16x32_bf16 v[40:43], v[212:215], v[220:223], v[2:5]
	v_mfma_f32_16x16x32_bf16 v[2:5], v[216:219], v[112:115], v[200:203]
	v_mfma_f32_16x16x32_bf16 v[36:39], v[188:191], v[220:223], v[2:5]
	v_mfma_f32_16x16x32_bf16 v[2:5], v[128:131], v[224:227], v[204:207]
	v_mfma_f32_16x16x32_bf16 v[24:27], v[212:215], v[228:231], v[2:5]
	v_mfma_f32_16x16x32_bf16 v[2:5], v[216:219], v[224:227], v[120:123]
	v_mfma_f32_16x16x32_bf16 v[20:23], v[188:191], v[228:231], v[2:5]
	v_mfma_f32_16x16x32_bf16 v[2:5], v[128:131], v[232:235], v[208:211]
	v_mfma_f32_16x16x32_bf16 v[8:11], v[212:215], v[236:239], v[2:5]
	v_mfma_f32_16x16x32_bf16 v[2:5], v[216:219], v[232:235], v[124:127]
	v_mfma_f32_16x16x32_bf16 v[4:7], v[188:191], v[236:239], v[2:5]
	s_setprio 0
	s_barrier
	s_mov_b64 s[18:19], 0
	s_branch .LBB0_919

; #define GAS __attribute__((address_space(1)))
; __device__ __forceinline__ unsigned pk2(float lo, float hi) { const f32x2_t v = {lo, hi}; const bf16x2_t b = __builtin_convertvector(v, bf16x2_t); return __builtin_bit_cast(unsigned, b); }
; __device__ __forceinline__ void norm_mod_phase(const Args& a, Frame& F, const float* gain, const float* modl, int sh_off, int sc_off, int nrows, const float* slab_gate) {
;     ...
;         for (int j = 0; j < 8; ++j) ss += (v[j][0] * v[j][0] + v[j][1] * v[j][1]) + (v[j][2] * v[j][2] + v[j][3] * v[j][3]);
;         const float rstd = 1.0f / sqrtf(wave_sum(ss) * (1.0f / D) + EPS);
;         const float* mb = modl + (size_t)b * MOD_LD;
;         GAS v2u* o8 = (GAS v2u*)(HN + (size_t)r * D) + F.lane;
; #pragma unroll
;         for (int j = 0; j < 8; ++j) { const int c = 256 * j + 4 * F.lane;
;             const f32x4 g = *(const GAS f32x4*)(gain + c), sh = *(const GAS f32x4*)(mb + sh_off + c), sc = *(const GAS f32x4*)(mb + sc_off + c);
;             const f32x4 y = (v[j] * rstd) * g * (sc + 1.0f) + sh;
;             v2u w; w.x = pk2(y[0], y[1]); w.y = pk2(y[2], y[3]); o8[64 * j] = w; }
.LBB0_1038:
	v_mul_f32_e32 v76, v70, v70
	v_mul_f32_e32 v77, v71, v71
	v_mul_f32_e32 v78, v66, v66
	v_mul_f32_e32 v79, v67, v67
	v_mul_f32_e32 v10, v72, v72
	v_mul_f32_e32 v11, v73, v73
	v_mul_f32_e32 v12, v68, v68
	v_mul_f32_e32 v13, v69, v69
	v_mov_b32_e32 v80, v76
	v_mov_b32_e32 v81, v78
	v_mov_b32_e32 v78, v77
	v_mul_f32_e32 v6, v64, v64
	v_mul_f32_e32 v7, v65, v65
	v_mul_f32_e32 v8, v62, v62
	v_mul_f32_e32 v9, v63, v63
	v_add_f32_e32 v76, v80, v78
	v_add_f32_e32 v77, v81, v79
	v_mov_b32_e32 v78, v10
	v_mov_b32_e32 v79, v12
	v_mov_b32_e32 v12, v11
	v_add_f32_e32 v10, v78, v12
	v_add_f32_e32 v11, v79, v13
	v_pk_mov_b32 v[12:13], v[8:9], v[6:7] op_sel:[1,0]
	v_mov_b32_e32 v9, v7
	v_mul_f32_e32 v0, v58, v58
	v_add_f32_e32 v10, v76, v10
	v_add_f32_e32 v11, v77, v11
	v_add_f32_e32 v6, v12, v8
	v_add_f32_e32 v7, v13, v9
	v_fma_f32 v8, v58, v58, v0
	v_fma_f32 v9, v59, v59, v0
	v_mul_f32_e32 v0, v60, v60
	v_add_f32_e32 v11, v10, v11
	v_add_f32_e32 v10, v10, v10
	v_add_f32_e32 v7, v6, v7
	v_add_f32_e32 v6, v6, v6
	v_fma_f32 v12, v60, v60, v0
	v_fma_f32 v13, v61, v61, v0
	v_mul_f32_e32 v8, v54, v54
	v_mul_f32_e32 v12, v55, v55
	v_mul_f32_e32 v6, v56, v56
	v_mul_f32_e32 v10, v57, v57
	v_mul_f32_e32 v2, v52, v52
	v_mul_f32_e32 v3, v53, v53
	v_mul_f32_e32 v4, v50, v50
	v_mul_f32_e32 v5, v51, v51
	v_add_f32_e32 v8, v8, v12
	v_add_f32_e32 v9, v9, v13
	v_add_f32_e32 v6, v6, v10
	v_add_f32_e32 v7, v7, v11
	v_mul_f32_e32 v0, v46, v46
	v_add_f32_e32 v6, v8, v6
	v_add_f32_e32 v7, v9, v7
	v_pk_mov_b32 v[8:9], v[4:5], v[2:3] op_sel:[1,0]
	v_mov_b32_e32 v5, v3
	v_add_f32_e32 v2, v8, v4
	v_add_f32_e32 v3, v9, v5
	v_fma_f32 v4, v46, v46, v0
	v_fma_f32 v5, v47, v47, v0
	v_mul_f32_e32 v0, v48, v48
	v_add_f32_e32 v7, v6, v7
	v_add_f32_e32 v6, v6, v6
	v_add_f32_e32 v3, v2, v3
	v_add_f32_e32 v2, v2, v2
	v_fma_f32 v8, v48, v48, v0
	v_fma_f32 v9, v49, v49, v0
	v_mul_f32_e32 v4, v42, v42
	v_mul_f32_e32 v8, v43, v43
	v_mul_f32_e32 v2, v44, v44
	v_mul_f32_e32 v6, v45, v45
	v_add_f32_e32 v4, v4, v8
	v_add_f32_e32 v5, v5, v9
	v_add_f32_e32 v2, v2, v6
	v_add_f32_e32 v3, v3, v7
	s_min_i32 s6, s12, 0x4000
	v_add_f32_e32 v2, v4, v2
	v_add_f32_e32 v3, v5, v3
	s_ashr_i32 s6, s6, 12
	v_add_f32_e32 v0, v2, v3
	v_lshl_add_u64 v[38:39], v[38:39], 0, s[74:75]
	s_nop 0
	v_add_f32_dpp v0, v0, v0 quad_perm:[1,0,3,2] row_mask:0xf bank_mask:0xf bound_ctrl:1
	s_nop 1
	v_add_f32_dpp v0, v0, v0 quad_perm:[2,3,0,1] row_mask:0xf bank_mask:0xf bound_ctrl:1
	s_nop 1
	v_add_f32_dpp v0, v0, v0 row_half_mirror row_mask:0xf bank_mask:0xf bound_ctrl:1
	s_nop 1
	v_add_f32_dpp v0, v0, v0 row_mirror row_mask:0xf bank_mask:0xf bound_ctrl:1
	s_nop 0
	v_readlane_b32 s7, v0, 16
	v_readlane_b32 s10, v0, 48
	v_readlane_b32 s8, v0, 0
	v_readlane_b32 s9, v0, 32
	v_mov_b32_e32 v2, s7
	v_mov_b32_e32 v3, s10
	v_add_f32_e32 v2, s8, v2
	v_add_f32_e32 v3, s9, v3
	s_mul_hi_i32 s7, s6, 0xc000
	v_add_f32_e32 v0, v2, v3
	v_fmamk_f32 v0, v0, 0x3a000000, v252
	v_cmp_gt_f32_e32 vcc, s55, v0
	v_mul_f32_e32 v2, 0x4f800000, v0
	s_mul_i32 s6, s6, 0xc000
	v_cndmask_b32_e32 v0, v0, v2, vcc
	v_sqrt_f32_e32 v2, v0
	s_add_u32 s6, s86, s6
	s_addc_u32 s7, s87, s7
	s_add_u32 s10, s6, 0x6000
	v_add_u32_e32 v3, -1, v2
	v_fma_f32 v4, -v3, v2, v0
	v_cmp_ge_f32_e64 s[8:9], 0, v4
	v_add_u32_e32 v4, 1, v2
	s_addc_u32 s11, s7, 0
	v_cndmask_b32_e64 v3, v2, v3, s[8:9]
	v_fma_f32 v2, -v4, v2, v0
	v_cmp_lt_f32_e64 s[8:9], 0, v2
	s_nop 1
	v_cndmask_b32_e64 v2, v3, v4, s[8:9]
	v_mul_f32_e32 v3, 0x37800000, v2
	v_cndmask_b32_e32 v2, v2, v3, vcc
	v_cmp_class_f32_e32 vcc, v0, v253
	s_nop 1
	v_cndmask_b32_e32 v0, v2, v0, vcc
	v_div_scale_f32 v2, s[8:9], v0, v0, 1.0
	v_rcp_f32_e32 v3, v2
	s_add_u32 s8, s6, 0x8000
	s_addc_u32 s9, s7, 0
	s_add_i32 s12, s12, s42
	v_fma_f32 v4, -v2, v3, 1.0
	v_fmac_f32_e32 v3, v4, v3
	v_div_scale_f32 v4, vcc, 1.0, v0, 1.0
	v_mul_f32_e32 v5, v4, v3
	v_fma_f32 v6, -v2, v5, v4
	v_fmac_f32_e32 v5, v6, v3
	v_fma_f32 v2, -v2, v5, v4
	v_div_fmas_f32 v2, v2, v3, v5
	v_div_fixup_f32 v0, v2, v0, 1.0
	global_load_dwordx4 v[6:9], v[18:19], off
	global_load_dwordx4 v[2:5], v15, s[10:11]
	global_load_dwordx4 v[10:13], v15, s[8:9]
	v_mul_f32_e32 v72, v72, v0
	v_mul_f32_e32 v73, v73, v0
	v_mul_f32_e32 v70, v70, v0
	v_mul_f32_e32 v71, v71, v0
	v_mul_f32_e32 v68, v68, v0
	v_mul_f32_e32 v69, v69, v0
	v_mul_f32_e32 v66, v66, v0
	v_mul_f32_e32 v67, v67, v0
	v_mul_f32_e32 v64, v64, v0
	v_mul_f32_e32 v65, v65, v0
	v_mul_f32_e32 v62, v62, v0
	v_mul_f32_e32 v63, v63, v0
	v_mul_f32_e32 v60, v60, v0
	v_mul_f32_e32 v61, v61, v0
	v_mul_f32_e32 v58, v58, v0
	v_mul_f32_e32 v59, v59, v0
	v_mul_f32_e32 v56, v56, v0
	v_mul_f32_e32 v57, v57, v0
	v_mul_f32_e32 v54, v54, v0
	v_mul_f32_e32 v55, v55, v0
	v_mul_f32_e32 v52, v52, v0
	v_mul_f32_e32 v53, v53, v0
	v_mul_f32_e32 v50, v50, v0
	v_mul_f32_e32 v51, v51, v0
	v_mul_f32_e32 v48, v48, v0
	v_mul_f32_e32 v49, v49, v0
	v_mul_f32_e32 v46, v46, v0
	v_mul_f32_e32 v47, v47, v0
	v_mul_f32_e32 v44, v44, v0
	v_mul_f32_e32 v45, v45, v0
	v_mul_f32_e32 v42, v42, v0
	v_mul_f32_e32 v43, v43, v0
	s_cmp_lt_i32 s12, s47
	s_waitcnt vmcnt(2)
	v_mul_f32_e32 v6, v6, v70
	v_mul_f32_e32 v7, v7, v71
	v_mul_f32_e32 v8, v8, v72
	v_mul_f32_e32 v9, v9, v73
	s_waitcnt vmcnt(0)
	v_add_f32_e32 v12, 1.0, v12
	v_add_f32_e32 v13, 1.0, v13
	v_add_f32_e32 v10, 1.0, v10
	v_add_f32_e32 v11, 1.0, v11
	v_fma_f32 v4, v12, v8, v4
	v_fma_f32 v5, v13, v9, v5
	v_fma_f32 v2, v10, v6, v2
	v_fma_f32 v3, v11, v7, v3
	s_nop 0
	v_cvt_pk_bf16_f32 v2, v2, v3
	v_cvt_pk_bf16_f32 v3, v4, v5
	global_store_dwordx2 v[40:41], v[2:3], off
	global_load_dwordx4 v[2:5], v[18:19], off offset:1024
	s_nop 0
	global_load_dwordx4 v[6:9], v82, s[10:11]
	global_load_dwordx4 v[10:13], v82, s[8:9]
	s_waitcnt vmcnt(2)
; #define GAS __attribute__((address_space(1)))
; __device__ __forceinline__ unsigned pk2(float lo, float hi) { const f32x2_t v = {lo, hi}; const bf16x2_t b = __builtin_convertvector(v, bf16x2_t); return __builtin_bit_cast(unsigned, b); }
; __device__ __forceinline__ void norm_mod_phase(const Args& a, Frame& F, const float* gain, const float* modl, int sh_off, int sc_off, int nrows, const float* slab_gate) {
;     ...
; #pragma unroll
;         for (int j = 0; j < 8; ++j) { const int c = 256 * j + 4 * F.lane;
;             const f32x4 g = *(const GAS f32x4*)(gain + c), sh = *(const GAS f32x4*)(mb + sh_off + c), sc = *(const GAS f32x4*)(mb + sc_off + c);
;             const f32x4 y = (v[j] * rstd) * g * (sc + 1.0f) + sh;
;             v2u w; w.x = pk2(y[0], y[1]); w.y = pk2(y[2], y[3]); o8[64 * j] = w; }
	v_mul_f32_e32 v2, v2, v66
	v_mul_f32_e32 v3, v3, v67
	v_mul_f32_e32 v4, v4, v68
	v_mul_f32_e32 v5, v5, v69
	s_waitcnt vmcnt(0)
	v_add_f32_e32 v12, 1.0, v12
	v_add_f32_e32 v13, 1.0, v13
	v_add_f32_e32 v10, 1.0, v10
	v_add_f32_e32 v11, 1.0, v11
	v_fma_f32 v4, v12, v4, v8
	v_fma_f32 v5, v13, v5, v9
	v_fma_f32 v2, v10, v2, v6
	v_fma_f32 v3, v11, v3, v7
	s_nop 0
	v_cvt_pk_bf16_f32 v2, v2, v3
	v_cvt_pk_bf16_f32 v3, v4, v5
	global_store_dwordx2 v[40:41], v[2:3], off offset:512
	global_load_dwordx4 v[2:5], v[18:19], off offset:2048
	s_nop 0
	global_load_dwordx4 v[6:9], v83, s[10:11]
	global_load_dwordx4 v[10:13], v83, s[8:9]
	s_waitcnt vmcnt(2)
	v_mul_f32_e32 v2, v2, v62
	v_mul_f32_e32 v3, v3, v63
	v_mul_f32_e32 v4, v4, v64
	v_mul_f32_e32 v5, v5, v65
	s_waitcnt vmcnt(0)
	v_add_f32_e32 v12, 1.0, v12
	v_add_f32_e32 v13, 1.0, v13
	v_add_f32_e32 v10, 1.0, v10
	v_add_f32_e32 v11, 1.0, v11
	v_fma_f32 v4, v4, v12, v8
	v_fma_f32 v5, v5, v13, v9
	v_fma_f32 v2, v2, v10, v6
	v_fma_f32 v3, v3, v11, v7
	s_nop 0
	v_cvt_pk_bf16_f32 v2, v2, v3
	v_cvt_pk_bf16_f32 v3, v4, v5
	global_store_dwordx2 v[40:41], v[2:3], off offset:1024
	global_load_dwordx4 v[2:5], v[18:19], off offset:3072
	s_nop 0
	global_load_dwordx4 v[6:9], v84, s[10:11]
	global_load_dwordx4 v[10:13], v84, s[8:9]
	s_waitcnt vmcnt(2)
	v_mul_f32_e32 v2, v58, v2
	v_mul_f32_e32 v3, v59, v3
	v_mul_f32_e32 v4, v60, v4
	v_mul_f32_e32 v5, v61, v5
	s_waitcnt vmcnt(0)
	v_add_f32_e32 v12, 1.0, v12
	v_add_f32_e32 v13, 1.0, v13
	v_add_f32_e32 v10, 1.0, v10
	v_add_f32_e32 v11, 1.0, v11
	v_fma_f32 v4, v4, v12, v8
	v_fma_f32 v5, v5, v13, v9
	v_fma_f32 v2, v2, v10, v6
	v_fma_f32 v3, v3, v11, v7
	s_nop 0
	v_cvt_pk_bf16_f32 v2, v2, v3
	v_cvt_pk_bf16_f32 v3, v4, v5
	global_store_dwordx2 v[40:41], v[2:3], off offset:1536
	global_load_dwordx4 v[2:5], v[20:21], off
	s_nop 0
	global_load_dwordx4 v[6:9], v85, s[10:11]
	global_load_dwordx4 v[10:13], v85, s[8:9]
	s_waitcnt vmcnt(2)
	v_mul_f32_e32 v2, v54, v2
	v_mul_f32_e32 v3, v55, v3
	v_mul_f32_e32 v4, v56, v4
	v_mul_f32_e32 v5, v57, v5
	s_waitcnt vmcnt(0)
	v_add_f32_e32 v12, 1.0, v12
	v_add_f32_e32 v13, 1.0, v13
	v_add_f32_e32 v10, 1.0, v10
	v_add_f32_e32 v11, 1.0, v11
	v_fma_f32 v4, v4, v12, v8
	v_fma_f32 v5, v5, v13, v9
	v_fma_f32 v2, v2, v10, v6
	v_fma_f32 v3, v3, v11, v7
	s_nop 0
	v_cvt_pk_bf16_f32 v2, v2, v3
	v_cvt_pk_bf16_f32 v3, v4, v5
	global_store_dwordx2 v[40:41], v[2:3], off offset:2048
	global_load_dwordx4 v[2:5], v[22:23], off
	s_nop 0
	global_load_dwordx4 v[6:9], v86, s[10:11]
	global_load_dwordx4 v[10:13], v86, s[8:9]
	s_waitcnt vmcnt(2)
	v_mul_f32_e32 v2, v50, v2
	v_mul_f32_e32 v3, v51, v3
	v_mul_f32_e32 v4, v52, v4
	v_mul_f32_e32 v5, v53, v5
	s_waitcnt vmcnt(0)
	v_add_f32_e32 v12, 1.0, v12
	v_add_f32_e32 v13, 1.0, v13
	v_add_f32_e32 v10, 1.0, v10
	v_add_f32_e32 v11, 1.0, v11
	v_fma_f32 v4, v4, v12, v8
	v_fma_f32 v5, v5, v13, v9
	v_fma_f32 v2, v2, v10, v6
	v_fma_f32 v3, v3, v11, v7
	s_nop 0
	v_cvt_pk_bf16_f32 v2, v2, v3
	v_cvt_pk_bf16_f32 v3, v4, v5
	global_store_dwordx2 v[40:41], v[2:3], off offset:2560
	global_load_dwordx4 v[2:5], v[24:25], off
	s_nop 0
	global_load_dwordx4 v[6:9], v87, s[10:11]
	global_load_dwordx4 v[10:13], v87, s[8:9]
	s_waitcnt vmcnt(2)
	v_mul_f32_e32 v2, v46, v2
	v_mul_f32_e32 v3, v47, v3
	v_mul_f32_e32 v4, v48, v4
	v_mul_f32_e32 v5, v49, v5
	s_waitcnt vmcnt(0)
	v_add_f32_e32 v12, 1.0, v12
	v_add_f32_e32 v13, 1.0, v13
	v_add_f32_e32 v10, 1.0, v10
	v_add_f32_e32 v11, 1.0, v11
	v_fma_f32 v4, v4, v12, v8
	v_fma_f32 v5, v5, v13, v9
	v_fma_f32 v2, v2, v10, v6
	v_fma_f32 v3, v3, v11, v7
	s_nop 0
	v_cvt_pk_bf16_f32 v2, v2, v3
	v_cvt_pk_bf16_f32 v3, v4, v5
	global_store_dwordx2 v[40:41], v[2:3], off offset:3072
	global_load_dwordx4 v[2:5], v[26:27], off
	s_nop 0
	global_load_dwordx4 v[6:9], v88, s[10:11]
	global_load_dwordx4 v[10:13], v88, s[8:9]
	s_waitcnt vmcnt(2)
	v_mul_f32_e32 v2, v42, v2
	v_mul_f32_e32 v3, v43, v3
	v_mul_f32_e32 v4, v44, v4
	v_mul_f32_e32 v5, v45, v5
	s_waitcnt vmcnt(0)
	v_add_f32_e32 v12, 1.0, v12
	v_add_f32_e32 v13, 1.0, v13
	v_add_f32_e32 v10, 1.0, v10
	v_add_f32_e32 v11, 1.0, v11
	v_fma_f32 v4, v4, v12, v8
	v_fma_f32 v5, v5, v13, v9
	v_fma_f32 v2, v2, v10, v6
	v_fma_f32 v3, v3, v11, v7
	s_nop 0
	v_cvt_pk_bf16_f32 v2, v2, v3
	v_cvt_pk_bf16_f32 v3, v4, v5
	global_store_dwordx2 v[40:41], v[2:3], off offset:3584
	s_cbranch_scc0 .LBB0_1041
; #define GAS __attribute__((address_space(1)))
; __device__ __forceinline__ unsigned xpk2(float lo, float hi) { if (XRES_F16) { const f32x2_t v = {lo, hi}; const f16x2_t h = __builtin_convertvector(v, f16x2_t); return __builtin_bit_cast(unsigned, h); } return pk2(lo, hi); }
; __device__ __forceinline__ float xlo(unsigned w) { if (XRES_F16) { const f16x2_t h = __builtin_bit_cast(f16x2_t, w); return (float)h[0]; } return __builtin_bit_cast(float, w << 16); }
; __device__ __forceinline__ float xhi(unsigned w) { if (XRES_F16) { const f16x2_t h = __builtin_bit_cast(f16x2_t, w); return (float)h[1]; } return __builtin_bit_cast(float, w & 0xffff0000u); }
; __device__ __forceinline__ void norm_mod_phase(const Args& a, Frame& F, const float* gain, const float* modl, int sh_off, int sc_off, int nrows, const float* slab_gate) {
;     ...
;     for (int r = gw; r < nrows; r += NGW) {
;         const int b = (r < ML) ? (r >> 12) : 4;
;         const GAS v2u* xr = (const GAS v2u*)(X + (size_t)r * D) + F.lane;
;         f32x4 v[8]; float ss = 0.f;
; #pragma unroll
;         for (int j = 0; j < 8; ++j) { const v2u w = xr[64 * j]; v[j] = (f32x4){xlo(w.x), xhi(w.x), xlo(w.y), xhi(w.y)}; }
;         if (slab_gate != nullptr && r >= ML) {
;             const GAS f32x4* sl = (const GAS f32x4*)((const float*)(a.ws + WS_SLAB) + (size_t)(r - ML) * D) + F.lane;
; #pragma unroll
;             for (int j = 0; j < 8; ++j) { const f32x4 p = (sl[64 * j] + sl[64 * j + (size_t)MC * D / 4]) + (sl[64 * j + 2 * ((size_t)MC * D / 4)] + sl[64 * j + 3 * ((size_t)MC * D / 4)]);
;                 v[j] += *(const GAS f32x4*)(slab_gate + 256 * j + 4 * F.lane) * p; v2u w; w.x = xpk2(v[j][0], v[j][1]); w.y = xpk2(v[j][2], v[j][3]); ((GAS v2u*)(X + (size_t)r * D) + F.lane)[64 * j] = w;
;                 v[j] = (f32x4){xlo(w.x), xhi(w.x), xlo(w.y), xhi(w.y)}; }
.LBB0_1039:
	v_lshlrev_b32_e32 v0, 3, v14
	v_lshl_add_u64 v[40:41], v[38:39], 0, v[0:1]
	v_add_co_u32_e32 v42, vcc, 0xf7800000, v40
	v_lshl_add_u64 v[2:3], v[40:41], 0, s[52:53]
	s_nop 0
	v_addc_co_u32_e32 v43, vcc, -1, v41, vcc
	global_load_dwordx2 v[4:5], v[2:3], off offset:512
	global_load_dwordx2 v[6:7], v[2:3], off offset:1024
	global_load_dwordx2 v[8:9], v[2:3], off offset:1536
	global_load_dwordx2 v[10:11], v[2:3], off offset:2048
	global_load_dwordx2 v[12:13], v[2:3], off offset:2560
	global_load_dwordx2 v[44:45], v[2:3], off offset:3072
	s_nop 0
	global_load_dwordx2 v[42:43], v[42:43], off
	s_nop 0
	global_load_dwordx2 v[76:77], v[2:3], off offset:3584
	s_cmpk_lt_i32 s12, 0x4000
	s_cselect_b64 s[6:7], -1, 0
	s_xor_b64 s[8:9], s[4:5], -1
	s_or_b64 s[6:7], s[8:9], s[6:7]
	s_and_b64 vcc, exec, s[6:7]
	s_waitcnt vmcnt(7)
	v_cvt_f32_f16_e32 v66, v4
	v_cvt_f32_f16_sdwa v67, v4 dst_sel:DWORD dst_unused:UNUSED_PAD src0_sel:WORD_1
	v_cvt_f32_f16_e32 v68, v5
	v_cvt_f32_f16_sdwa v69, v5 dst_sel:DWORD dst_unused:UNUSED_PAD src0_sel:WORD_1
	s_waitcnt vmcnt(6)
	v_cvt_f32_f16_e32 v62, v6
	v_cvt_f32_f16_sdwa v63, v6 dst_sel:DWORD dst_unused:UNUSED_PAD src0_sel:WORD_1
	v_cvt_f32_f16_e32 v64, v7
	v_cvt_f32_f16_sdwa v65, v7 dst_sel:DWORD dst_unused:UNUSED_PAD src0_sel:WORD_1
	s_waitcnt vmcnt(5)
	v_cvt_f32_f16_e32 v58, v8
	v_cvt_f32_f16_sdwa v59, v8 dst_sel:DWORD dst_unused:UNUSED_PAD src0_sel:WORD_1
	v_cvt_f32_f16_e32 v60, v9
	v_cvt_f32_f16_sdwa v61, v9 dst_sel:DWORD dst_unused:UNUSED_PAD src0_sel:WORD_1
	s_waitcnt vmcnt(4)
	v_cvt_f32_f16_e32 v54, v10
	v_cvt_f32_f16_sdwa v55, v10 dst_sel:DWORD dst_unused:UNUSED_PAD src0_sel:WORD_1
	v_cvt_f32_f16_e32 v56, v11
	v_cvt_f32_f16_sdwa v57, v11 dst_sel:DWORD dst_unused:UNUSED_PAD src0_sel:WORD_1
	s_waitcnt vmcnt(3)
	v_cvt_f32_f16_e32 v50, v12
	v_cvt_f32_f16_sdwa v51, v12 dst_sel:DWORD dst_unused:UNUSED_PAD src0_sel:WORD_1
	v_cvt_f32_f16_e32 v52, v13
	v_cvt_f32_f16_sdwa v53, v13 dst_sel:DWORD dst_unused:UNUSED_PAD src0_sel:WORD_1
	s_waitcnt vmcnt(2)
	v_cvt_f32_f16_e32 v46, v44
	v_cvt_f32_f16_sdwa v47, v44 dst_sel:DWORD dst_unused:UNUSED_PAD src0_sel:WORD_1
	v_cvt_f32_f16_e32 v48, v45
	v_cvt_f32_f16_sdwa v49, v45 dst_sel:DWORD dst_unused:UNUSED_PAD src0_sel:WORD_1
	s_waitcnt vmcnt(1)
	v_cvt_f32_f16_e32 v70, v42
	v_cvt_f32_f16_sdwa v71, v42 dst_sel:DWORD dst_unused:UNUSED_PAD src0_sel:WORD_1
	v_cvt_f32_f16_e32 v72, v43
	v_cvt_f32_f16_sdwa v73, v43 dst_sel:DWORD dst_unused:UNUSED_PAD src0_sel:WORD_1
	s_waitcnt vmcnt(0)
	v_cvt_f32_f16_e32 v42, v76
	v_cvt_f32_f16_sdwa v43, v76 dst_sel:DWORD dst_unused:UNUSED_PAD src0_sel:WORD_1
	v_cvt_f32_f16_e32 v44, v77
	v_cvt_f32_f16_sdwa v45, v77 dst_sel:DWORD dst_unused:UNUSED_PAD src0_sel:WORD_1
	s_cbranch_vccnz .LBB0_1038
	v_mov_b64_e32 v[4:5], s[0:1]
	flat_load_dwordx2 v[4:5], v[4:5] offset:152
	s_add_i32 s84, s12, 0xffffc000
	s_lshl_b64 s[6:7], s[84:85], 13
	v_lshlrev_b32_e32 v0, 4, v14
	s_waitcnt vmcnt(0) lgkmcnt(0)
	v_lshl_add_u64 v[4:5], v[4:5], 0, s[6:7]
	v_lshl_add_u64 v[94:95], v[4:5], 0, v[0:1]
	s_mov_b64 s[6:7], 0x58400000
	v_lshl_add_u64 v[12:13], v[94:95], 0, s[6:7]
	s_mov_b32 s6, 0x58401000
	v_add_co_u32_e32 v4, vcc, s6, v94
	s_mov_b32 s6, 0x58c00000
	s_nop 0
	v_addc_co_u32_e32 v5, vcc, 0, v95, vcc
	v_add_co_u32_e32 v76, vcc, s6, v94
	s_mov_b32 s6, 0x58c01000
	s_nop 0
	v_addc_co_u32_e32 v77, vcc, 0, v95, vcc
	v_add_co_u32_e32 v6, vcc, s6, v94
	global_load_dwordx4 v[8:11], v[4:5], off offset:-4096
	s_nop 0
	v_addc_co_u32_e32 v7, vcc, 0, v95, vcc
	global_load_dwordx4 v[78:81], v[6:7], off offset:-4096
	s_mov_b32 s6, 0x59400000
	s_waitcnt vmcnt(0)
	v_add_f32_e32 v100, v8, v78
	v_add_f32_e32 v101, v9, v79
	v_add_co_u32_e32 v78, vcc, s6, v94
	s_mov_b32 s6, 0x59401000
	s_nop 0
	v_addc_co_u32_e32 v79, vcc, 0, v95, vcc
	v_add_co_u32_e32 v8, vcc, s6, v94
	s_mov_b32 s6, 0x59c00000
	s_nop 0
	v_addc_co_u32_e32 v9, vcc, 0, v95, vcc
	v_add_f32_e32 v98, v10, v80
	v_add_f32_e32 v99, v11, v81
	v_add_co_u32_e32 v80, vcc, s6, v94
	s_mov_b32 s6, 0x59c01000
	s_nop 0
	v_addc_co_u32_e32 v81, vcc, 0, v95, vcc
	v_add_co_u32_e32 v10, vcc, s6, v94
	global_load_dwordx4 v[90:93], v[8:9], off offset:-4096
	s_nop 0
	v_addc_co_u32_e32 v11, vcc, 0, v95, vcc
	global_load_dwordx4 v[94:97], v[10:11], off offset:-4096
	s_waitcnt vmcnt(0)
	v_add_f32_e32 v92, v92, v96
	v_add_f32_e32 v93, v93, v97
	v_add_f32_e32 v90, v90, v94
	v_add_f32_e32 v91, v91, v95
	v_add_f32_e32 v94, v98, v92
	v_add_f32_e32 v95, v99, v93
	v_add_f32_e32 v96, v100, v90
	v_add_f32_e32 v97, v101, v91
	global_load_dwordx4 v[90:93], v[16:17], off
	s_waitcnt vmcnt(0)
	v_fma_f32 v72, v92, v94, v72
	v_fma_f32 v73, v93, v95, v73
	v_fma_f32 v70, v90, v96, v70
	v_fma_f32 v71, v91, v97, v71
	v_cvt_pk_f16_f32 v91, v72, v73
	v_cvt_pk_f16_f32 v90, v70, v71
	global_store_dwordx2 v[2:3], v[90:91], off
	v_cvt_f32_f16_e32 v70, v90
	v_cvt_f32_f16_sdwa v71, v90 dst_sel:DWORD dst_unused:UNUSED_PAD src0_sel:WORD_1
	v_cvt_f32_f16_e32 v72, v91
	v_cvt_f32_f16_sdwa v73, v91 dst_sel:DWORD dst_unused:UNUSED_PAD src0_sel:WORD_1
	global_load_dwordx4 v[90:93], v[12:13], off offset:1024
	global_load_dwordx4 v[94:97], v[76:77], off offset:1024
	s_waitcnt vmcnt(0)
	v_add_f32_e32 v98, v92, v96
	v_add_f32_e32 v99, v93, v97
	v_add_f32_e32 v100, v90, v94
	v_add_f32_e32 v101, v91, v95
	global_load_dwordx4 v[90:93], v[78:79], off offset:1024
	global_load_dwordx4 v[94:97], v[80:81], off offset:1024
	s_waitcnt vmcnt(0)
	v_add_f32_e32 v92, v92, v96
	v_add_f32_e32 v93, v93, v97
	v_add_f32_e32 v90, v90, v94
	v_add_f32_e32 v91, v91, v95
	v_add_f32_e32 v94, v98, v92
	v_add_f32_e32 v95, v99, v93
	v_add_f32_e32 v96, v100, v90
	v_add_f32_e32 v97, v101, v91
	global_load_dwordx4 v[90:93], v[28:29], off offset:1024
	s_waitcnt vmcnt(0)
; #define GAS __attribute__((address_space(1)))
; __device__ __forceinline__ unsigned xpk2(float lo, float hi) { if (XRES_F16) { const f32x2_t v = {lo, hi}; const f16x2_t h = __builtin_convertvector(v, f16x2_t); return __builtin_bit_cast(unsigned, h); } return pk2(lo, hi); }
; __device__ __forceinline__ float xlo(unsigned w) { if (XRES_F16) { const f16x2_t h = __builtin_bit_cast(f16x2_t, w); return (float)h[0]; } return __builtin_bit_cast(float, w << 16); }
; __device__ __forceinline__ float xhi(unsigned w) { if (XRES_F16) { const f16x2_t h = __builtin_bit_cast(f16x2_t, w); return (float)h[1]; } return __builtin_bit_cast(float, w & 0xffff0000u); }
; __device__ __forceinline__ void norm_mod_phase(const Args& a, Frame& F, const float* gain, const float* modl, int sh_off, int sc_off, int nrows, const float* slab_gate) {
;     ...
;         if (slab_gate != nullptr && r >= ML) {
;             const GAS f32x4* sl = (const GAS f32x4*)((const float*)(a.ws + WS_SLAB) + (size_t)(r - ML) * D) + F.lane;
; #pragma unroll
;             for (int j = 0; j < 8; ++j) { const f32x4 p = (sl[64 * j] + sl[64 * j + (size_t)MC * D / 4]) + (sl[64 * j + 2 * ((size_t)MC * D / 4)] + sl[64 * j + 3 * ((size_t)MC * D / 4)]);
;                 v[j] += *(const GAS f32x4*)(slab_gate + 256 * j + 4 * F.lane) * p; v2u w; w.x = xpk2(v[j][0], v[j][1]); w.y = xpk2(v[j][2], v[j][3]); ((GAS v2u*)(X + (size_t)r * D) + F.lane)[64 * j] = w;
;                 v[j] = (f32x4){xlo(w.x), xhi(w.x), xlo(w.y), xhi(w.y)}; }
	v_fma_f32 v68, v92, v94, v68
	v_fma_f32 v69, v93, v95, v69
	v_fma_f32 v66, v90, v96, v66
	v_fma_f32 v67, v91, v97, v67
	v_cvt_pk_f16_f32 v91, v68, v69
	v_cvt_pk_f16_f32 v90, v66, v67
	global_store_dwordx2 v[2:3], v[90:91], off offset:512
	v_cvt_f32_f16_e32 v66, v90
	v_cvt_f32_f16_sdwa v67, v90 dst_sel:DWORD dst_unused:UNUSED_PAD src0_sel:WORD_1
	v_cvt_f32_f16_e32 v68, v91
	v_cvt_f32_f16_sdwa v69, v91 dst_sel:DWORD dst_unused:UNUSED_PAD src0_sel:WORD_1
	global_load_dwordx4 v[90:93], v[12:13], off offset:2048
	global_load_dwordx4 v[94:97], v[76:77], off offset:2048
	s_waitcnt vmcnt(0)
	v_add_f32_e32 v98, v92, v96
	v_add_f32_e32 v99, v93, v97
	v_add_f32_e32 v100, v90, v94
	v_add_f32_e32 v101, v91, v95
	global_load_dwordx4 v[90:93], v[78:79], off offset:2048
	global_load_dwordx4 v[94:97], v[80:81], off offset:2048
	s_waitcnt vmcnt(0)
	v_add_f32_e32 v92, v92, v96
	v_add_f32_e32 v93, v93, v97
	v_add_f32_e32 v90, v90, v94
	v_add_f32_e32 v91, v91, v95
	v_add_f32_e32 v94, v98, v92
	v_add_f32_e32 v95, v99, v93
	v_add_f32_e32 v96, v100, v90
	v_add_f32_e32 v97, v101, v91
	global_load_dwordx4 v[90:93], v[28:29], off offset:2048
	s_waitcnt vmcnt(0)
	v_fma_f32 v64, v92, v94, v64
	v_fma_f32 v65, v93, v95, v65
	v_fma_f32 v62, v90, v96, v62
	v_fma_f32 v63, v91, v97, v63
	v_cvt_pk_f16_f32 v91, v64, v65
	v_cvt_pk_f16_f32 v90, v62, v63
	global_store_dwordx2 v[2:3], v[90:91], off offset:1024
	v_cvt_f32_f16_e32 v62, v90
	v_cvt_f32_f16_sdwa v63, v90 dst_sel:DWORD dst_unused:UNUSED_PAD src0_sel:WORD_1
	v_cvt_f32_f16_e32 v64, v91
	v_cvt_f32_f16_sdwa v65, v91 dst_sel:DWORD dst_unused:UNUSED_PAD src0_sel:WORD_1
	global_load_dwordx4 v[90:93], v[12:13], off offset:3072
	global_load_dwordx4 v[94:97], v[76:77], off offset:3072
	s_waitcnt vmcnt(0)
	v_add_f32_e32 v12, v92, v96
	v_add_f32_e32 v13, v93, v97
	v_add_f32_e32 v94, v90, v94
	v_add_f32_e32 v95, v91, v95
	global_load_dwordx4 v[76:79], v[78:79], off offset:3072
	s_nop 0
	global_load_dwordx4 v[90:93], v[80:81], off offset:3072
	s_waitcnt vmcnt(0)
	v_add_f32_e32 v78, v78, v92
	v_add_f32_e32 v79, v79, v93
	v_add_f32_e32 v76, v76, v90
	v_add_f32_e32 v77, v77, v91
	v_add_f32_e32 v12, v12, v78
	v_add_f32_e32 v13, v13, v79
	v_add_f32_e32 v80, v94, v76
	v_add_f32_e32 v81, v95, v77
	global_load_dwordx4 v[76:79], v[28:29], off offset:3072
	s_waitcnt vmcnt(0)
	v_fma_f32 v12, v78, v12, v60
	v_fma_f32 v13, v79, v13, v61
	v_fma_f32 v58, v76, v80, v58
	v_fma_f32 v59, v77, v81, v59
	v_cvt_pk_f16_f32 v61, v12, v13
	v_cvt_pk_f16_f32 v60, v58, v59
	global_store_dwordx2 v[2:3], v[60:61], off offset:1536
	global_load_dwordx4 v[76:79], v[4:5], off
	global_load_dwordx4 v[90:93], v[6:7], off
	v_cvt_f32_f16_e32 v58, v60
	v_cvt_f32_f16_sdwa v59, v60 dst_sel:DWORD dst_unused:UNUSED_PAD src0_sel:WORD_1
	v_cvt_f32_f16_e32 v60, v61
	v_cvt_f32_f16_sdwa v61, v61 dst_sel:DWORD dst_unused:UNUSED_PAD src0_sel:WORD_1
	s_waitcnt vmcnt(0)
	v_add_f32_e32 v12, v78, v92
	v_add_f32_e32 v13, v79, v93
	v_add_f32_e32 v80, v76, v90
	v_add_f32_e32 v81, v77, v91
	global_load_dwordx4 v[76:79], v[8:9], off
	global_load_dwordx4 v[90:93], v[10:11], off
	s_waitcnt vmcnt(0)
	v_add_f32_e32 v78, v78, v92
	v_add_f32_e32 v79, v79, v93
	v_add_f32_e32 v76, v76, v90
	v_add_f32_e32 v77, v77, v91
	v_add_f32_e32 v12, v12, v78
	v_add_f32_e32 v13, v13, v79
	v_add_f32_e32 v80, v80, v76
	v_add_f32_e32 v81, v81, v77
	global_load_dwordx4 v[76:79], v[30:31], off
	s_waitcnt vmcnt(0)
; #define GAS __attribute__((address_space(1)))
; __device__ __forceinline__ unsigned xpk2(float lo, float hi) { if (XRES_F16) { const f32x2_t v = {lo, hi}; const f16x2_t h = __builtin_convertvector(v, f16x2_t); return __builtin_bit_cast(unsigned, h); } return pk2(lo, hi); }
; __device__ __forceinline__ float xlo(unsigned w) { if (XRES_F16) { const f16x2_t h = __builtin_bit_cast(f16x2_t, w); return (float)h[0]; } return __builtin_bit_cast(float, w << 16); }
; __device__ __forceinline__ float xhi(unsigned w) { if (XRES_F16) { const f16x2_t h = __builtin_bit_cast(f16x2_t, w); return (float)h[1]; } return __builtin_bit_cast(float, w & 0xffff0000u); }
; __device__ __forceinline__ void norm_mod_phase(const Args& a, Frame& F, const float* gain, const float* modl, int sh_off, int sc_off, int nrows, const float* slab_gate) {
;     ...
;         if (slab_gate != nullptr && r >= ML) {
;             const GAS f32x4* sl = (const GAS f32x4*)((const float*)(a.ws + WS_SLAB) + (size_t)(r - ML) * D) + F.lane;
; #pragma unroll
;             for (int j = 0; j < 8; ++j) { const f32x4 p = (sl[64 * j] + sl[64 * j + (size_t)MC * D / 4]) + (sl[64 * j + 2 * ((size_t)MC * D / 4)] + sl[64 * j + 3 * ((size_t)MC * D / 4)]);
;                 v[j] += *(const GAS f32x4*)(slab_gate + 256 * j + 4 * F.lane) * p; v2u w; w.x = xpk2(v[j][0], v[j][1]); w.y = xpk2(v[j][2], v[j][3]); ((GAS v2u*)(X + (size_t)r * D) + F.lane)[64 * j] = w;
;                 v[j] = (f32x4){xlo(w.x), xhi(w.x), xlo(w.y), xhi(w.y)}; }
	v_fma_f32 v12, v78, v12, v56
	v_fma_f32 v13, v79, v13, v57
	v_fma_f32 v54, v76, v80, v54
	v_fma_f32 v55, v77, v81, v55
	v_cvt_pk_f16_f32 v57, v12, v13
	v_cvt_pk_f16_f32 v56, v54, v55
	global_store_dwordx2 v[2:3], v[56:57], off offset:2048
	global_load_dwordx4 v[76:79], v[4:5], off offset:1024
	global_load_dwordx4 v[90:93], v[6:7], off offset:1024
	v_cvt_f32_f16_e32 v54, v56
	v_cvt_f32_f16_sdwa v55, v56 dst_sel:DWORD dst_unused:UNUSED_PAD src0_sel:WORD_1
	v_cvt_f32_f16_e32 v56, v57
	v_cvt_f32_f16_sdwa v57, v57 dst_sel:DWORD dst_unused:UNUSED_PAD src0_sel:WORD_1
	s_waitcnt vmcnt(0)
	v_add_f32_e32 v12, v78, v92
	v_add_f32_e32 v13, v79, v93
	v_add_f32_e32 v80, v76, v90
	v_add_f32_e32 v81, v77, v91
	global_load_dwordx4 v[76:79], v[8:9], off offset:1024
	global_load_dwordx4 v[90:93], v[10:11], off offset:1024
	s_waitcnt vmcnt(0)
	v_add_f32_e32 v78, v78, v92
	v_add_f32_e32 v79, v79, v93
	v_add_f32_e32 v76, v76, v90
	v_add_f32_e32 v77, v77, v91
	v_add_f32_e32 v12, v12, v78
	v_add_f32_e32 v13, v13, v79
	v_add_f32_e32 v80, v80, v76
	v_add_f32_e32 v81, v81, v77
	global_load_dwordx4 v[76:79], v[32:33], off
	s_waitcnt vmcnt(0)
	v_fma_f32 v12, v78, v12, v52
	v_fma_f32 v13, v79, v13, v53
	v_fma_f32 v50, v76, v80, v50
	v_fma_f32 v51, v77, v81, v51
	v_cvt_pk_f16_f32 v53, v12, v13
	v_cvt_pk_f16_f32 v52, v50, v51
	global_store_dwordx2 v[2:3], v[52:53], off offset:2560
	global_load_dwordx4 v[76:79], v[4:5], off offset:2048
	global_load_dwordx4 v[90:93], v[6:7], off offset:2048
	v_cvt_f32_f16_e32 v50, v52
	v_cvt_f32_f16_sdwa v51, v52 dst_sel:DWORD dst_unused:UNUSED_PAD src0_sel:WORD_1
	v_cvt_f32_f16_e32 v52, v53
	v_cvt_f32_f16_sdwa v53, v53 dst_sel:DWORD dst_unused:UNUSED_PAD src0_sel:WORD_1
	s_waitcnt vmcnt(0)
	v_add_f32_e32 v12, v78, v92
	v_add_f32_e32 v13, v79, v93
	v_add_f32_e32 v80, v76, v90
	v_add_f32_e32 v81, v77, v91
	global_load_dwordx4 v[76:79], v[8:9], off offset:2048
	global_load_dwordx4 v[90:93], v[10:11], off offset:2048
	s_waitcnt vmcnt(0)
	v_add_f32_e32 v78, v78, v92
	v_add_f32_e32 v79, v79, v93
	v_add_f32_e32 v76, v76, v90
	v_add_f32_e32 v77, v77, v91
	v_add_f32_e32 v12, v12, v78
	v_add_f32_e32 v13, v13, v79
	v_add_f32_e32 v80, v80, v76
	v_add_f32_e32 v81, v81, v77
	global_load_dwordx4 v[76:79], v[34:35], off
	s_waitcnt vmcnt(0)
	v_fma_f32 v12, v78, v12, v48
	v_fma_f32 v13, v79, v13, v49
	v_fma_f32 v46, v76, v80, v46
	v_fma_f32 v47, v77, v81, v47
	v_cvt_pk_f16_f32 v49, v12, v13
	v_cvt_pk_f16_f32 v48, v46, v47
	global_store_dwordx2 v[2:3], v[48:49], off offset:3072
	global_load_dwordx4 v[76:79], v[4:5], off offset:3072
	s_nop 0
	global_load_dwordx4 v[4:7], v[6:7], off offset:3072
	v_cvt_f32_f16_e32 v46, v48
	v_cvt_f32_f16_sdwa v47, v48 dst_sel:DWORD dst_unused:UNUSED_PAD src0_sel:WORD_1
	v_cvt_f32_f16_e32 v48, v49
	v_cvt_f32_f16_sdwa v49, v49 dst_sel:DWORD dst_unused:UNUSED_PAD src0_sel:WORD_1
	s_waitcnt vmcnt(0)
	v_add_f32_e32 v12, v78, v6
	v_add_f32_e32 v13, v79, v7
	v_add_f32_e32 v76, v76, v4
	v_add_f32_e32 v77, v77, v5
	global_load_dwordx4 v[4:7], v[8:9], off offset:3072
	s_nop 0
	global_load_dwordx4 v[8:11], v[10:11], off offset:3072
	s_waitcnt vmcnt(0)
	v_add_f32_e32 v6, v6, v10
	v_add_f32_e32 v7, v7, v11
	v_add_f32_e32 v4, v4, v8
	v_add_f32_e32 v5, v5, v9
	v_add_f32_e32 v8, v12, v6
	v_add_f32_e32 v9, v13, v7
	v_add_f32_e32 v10, v76, v4
	v_add_f32_e32 v11, v77, v5
	global_load_dwordx4 v[4:7], v[36:37], off
	s_waitcnt vmcnt(0)
	v_fma_f32 v6, v6, v8, v44
	v_fma_f32 v7, v7, v9, v45
	v_fma_f32 v4, v4, v10, v42
	v_fma_f32 v5, v5, v11, v43
	s_nop 0
	v_cvt_pk_f16_f32 v4, v4, v5
	v_cvt_pk_f16_f32 v5, v6, v7
	v_cvt_f32_f16_e32 v42, v4
	v_cvt_f32_f16_sdwa v43, v4 dst_sel:DWORD dst_unused:UNUSED_PAD src0_sel:WORD_1
	v_cvt_f32_f16_e32 v44, v5
	v_cvt_f32_f16_sdwa v45, v5 dst_sel:DWORD dst_unused:UNUSED_PAD src0_sel:WORD_1
	global_store_dwordx2 v[2:3], v[4:5], off offset:3584
	s_branch .LBB0_1038

; #define GAS __attribute__((address_space(1)))
; #define LAS __attribute__((address_space(3)))
; __device__ __forceinline__ void relaunder(Frame& F) { int t = mk_tid(); asm volatile("" : "+v"(t)); F.tid = t; F.lane = t & 63; F.wave = __builtin_amdgcn_readfirstlane(t >> 6); }
; #define NR_LOAD(dst, k_) do { const GAS v2u* xr_ = (const GAS v2u*)(X + (size_t)(nw + 2048 * (k_)) * D) + F.lane; \
;         _Pragma("unroll") for (int j = 0; j < 8; ++j) dst[j] = __builtin_nontemporal_load(xr_ + 64 * j); } while (0)
; __device__ __forceinline__ void norm_mod_phase2(const Args& a, Frame& F, const float* gain, const float* modl, int sh_off, int sc_off, int nrows, const float* slab_gate) {
;     relaunder(F);
;     static_assert(ML == 8 * 2048 && MC <= 2048, "8 latent rows and at most one context row per wave of 2048");
;     const int nw = F.vcu * NWAVES + F.wave;
;     bf16* X = (bf16*)(a.ws + WS_X); bf16* HN = (bf16*)(a.ws + WS_HN);
;     LAS float* CA = (LAS float*)F.lds; LAS float* CB = CA + 5 * D;
;     v2u r0[8], r1[8], r2[8], r3[8], r4[8], r5[8], r6[8], r7[8];
;     ...
;     NR_LOAD(r0, 0); NR_LOAD(r1, 1); NR_LOAD(r2, 2); NR_LOAD(r3, 3); NR_LOAD(r4, 4); NR_LOAD(r5, 5); NR_LOAD(r6, 6); NR_LOAD(r7, 7);
;     { const GAS f32x4* g4 = (const GAS f32x4*)gain;
;       for (int q = F.tid; q < 5 * D / 4; q += NWAVES * 64) { const int bq = q >> 9, cq = q & 511; const GAS f32x4* mb4 = (const GAS f32x4*)(modl + (size_t)bq * MOD_LD);
;           ((LAS f32x4*)CA)[q] = g4[cq] * (mb4[sc_off / 4 + cq] + 1.0f); ((LAS f32x4*)CB)[q] = mb4[sh_off / 4 + cq]; } }
.LBB0_1042:
	s_andn2_b64 vcc, exec, s[8:9]
	s_cbranch_vccnz .LBB0_1051
	s_getreg_b32 s6, hwreg(HW_REG_HW_ID, 0, 6)
	s_lshl_b32 s6, s6, 2
	s_add_i32 s6, s6, 0
	s_add_i32 s6, s6, 0x20540
	v_mov_b32_e32 v0, s6
	ds_read_b32 v0, v0
	v_mov_b64_e32 v[2:3], s[0:1]
	v_mov_b32_e32 v7, v1
	s_waitcnt lgkmcnt(0)
	v_readfirstlane_b32 s6, v0
	v_mbcnt_lo_u32_b32 v0, -1, 0
	v_mbcnt_hi_u32_b32 v0, -1, v0
	s_nop 1
	v_lshl_add_u32 v142, s6, 6, v0
	v_mov_b32_e32 v136, s72
	v_mov_b32_e32 v137, s73
	v_readfirstlane_b32 s6, v142
	s_ashr_i32 s6, s6, 6
	s_add_i32 s10, s6, s91
	s_mov_b64 s[6:7], 0x400000
	s_ashr_i32 s11, s10, 31
	v_and_b32_e32 v147, 63, v142
	s_add_i32 s78, s10, 0x800
	v_lshlrev_b32_e32 v6, 3, v147
	s_ashr_i32 s79, s78, 31
	s_add_i32 s36, s10, 0x1000
	s_ashr_i32 s37, s36, 31
	s_add_i32 s30, s10, 0x1800
	s_ashr_i32 s31, s30, 31
	s_add_i32 s26, s10, 0x2000
	s_ashr_i32 s27, s26, 31
	s_add_i32 s22, s10, 0x2800
	s_ashr_i32 s23, s22, 31
	s_add_i32 s18, s10, 0x3000
	s_ashr_i32 s19, s18, 31
	s_add_i32 s14, s10, 0x3800
	s_ashr_i32 s15, s14, 31
	s_waitcnt vmcnt(0) lgkmcnt(0)
	v_lshl_add_u64 v[8:9], v[136:137], 0, s[6:7]
	s_lshl_b64 s[6:7], s[10:11], 12
	v_lshl_add_u64 v[2:3], v[8:9], 0, s[6:7]
	v_lshl_add_u64 v[2:3], v[2:3], 0, v[6:7]
	s_lshl_b64 s[6:7], s[78:79], 12
	v_and_b32_e32 v184, 0x1ff, v142
	v_lshlrev_b32_e32 v184, 4, v184
	v_mov_b32_e32 v185, 0
	v_mov_b32_e32 v186, s76
	v_lshlrev_b32_e32 v186, 13, v186
	v_mov_b32_e32 v187, 0
	v_lshl_add_u64 v[188:189], v[74:75], 0, v[186:187]
	v_lshl_add_u64 v[188:189], v[188:189], 0, v[184:185]
	global_load_dwordx4 v[192:195], v[188:189], off
	v_add_u32_e32 v196, 0x8000, v184
	v_add_u32_e32 v201, 0x6000, v184
	v_add_u32_e32 v197, 0x14000, v184
	v_add_u32_e32 v202, 0x12000, v184
	v_add_u32_e32 v198, 0x20000, v184
	v_add_u32_e32 v203, 0x1e000, v184
	v_add_u32_e32 v199, 0x2c000, v184
	v_add_u32_e32 v204, 0x2a000, v184
	v_add_u32_e32 v200, 0x38000, v184
	v_add_u32_e32 v205, 0x36000, v184
	global_load_dwordx4 v[208:211], v196, s[86:87]
	global_load_dwordx4 v[228:231], v201, s[86:87]
	global_load_dwordx4 v[212:215], v197, s[86:87]
	global_load_dwordx4 v[232:235], v202, s[86:87]
	global_load_dwordx4 v[216:219], v198, s[86:87]
	global_load_dwordx4 v[236:239], v203, s[86:87]
	global_load_dwordx4 v[220:223], v199, s[86:87]
	global_load_dwordx4 v[240:243], v204, s[86:87]
	global_load_dwordx4 v[224:227], v200, s[86:87]
	global_load_dwordx4 v[244:247], v205, s[86:87]
	global_load_dwordx2 v[140:141], v[2:3], off nt
	global_load_dwordx2 v[138:139], v[2:3], off offset:512 nt
	global_load_dwordx2 v[134:135], v[2:3], off offset:1024 nt
	global_load_dwordx2 v[132:133], v[2:3], off offset:1536 nt
	global_load_dwordx2 v[130:131], v[2:3], off offset:2048 nt
	global_load_dwordx2 v[128:129], v[2:3], off offset:2560 nt
	global_load_dwordx2 v[126:127], v[2:3], off offset:3072 nt
	global_load_dwordx2 v[124:125], v[2:3], off offset:3584 nt
	v_lshl_add_u64 v[2:3], v[8:9], 0, s[6:7]
	v_lshl_add_u64 v[2:3], v[2:3], 0, v[6:7]
	s_lshl_b64 s[6:7], s[36:37], 12
	global_load_dwordx2 v[122:123], v[2:3], off nt
	global_load_dwordx2 v[120:121], v[2:3], off offset:512 nt
	global_load_dwordx2 v[118:119], v[2:3], off offset:1024 nt
	global_load_dwordx2 v[116:117], v[2:3], off offset:1536 nt
	global_load_dwordx2 v[114:115], v[2:3], off offset:2048 nt
	global_load_dwordx2 v[112:113], v[2:3], off offset:2560 nt
	global_load_dwordx2 v[110:111], v[2:3], off offset:3072 nt
	global_load_dwordx2 v[108:109], v[2:3], off offset:3584 nt
	v_lshl_add_u64 v[2:3], v[8:9], 0, s[6:7]
	v_lshl_add_u64 v[2:3], v[2:3], 0, v[6:7]
	s_lshl_b64 s[6:7], s[30:31], 12
	global_load_dwordx2 v[106:107], v[2:3], off nt
	global_load_dwordx2 v[104:105], v[2:3], off offset:512 nt
	global_load_dwordx2 v[102:103], v[2:3], off offset:1024 nt
	global_load_dwordx2 v[100:101], v[2:3], off offset:1536 nt
	global_load_dwordx2 v[98:99], v[2:3], off offset:2048 nt
	global_load_dwordx2 v[96:97], v[2:3], off offset:2560 nt
	global_load_dwordx2 v[94:95], v[2:3], off offset:3072 nt
	global_load_dwordx2 v[92:93], v[2:3], off offset:3584 nt
	v_lshl_add_u64 v[2:3], v[8:9], 0, s[6:7]
	v_lshl_add_u64 v[2:3], v[2:3], 0, v[6:7]
	s_lshl_b64 s[6:7], s[26:27], 12
	global_load_dwordx2 v[90:91], v[2:3], off nt
	global_load_dwordx2 v[88:89], v[2:3], off offset:512 nt
	global_load_dwordx2 v[86:87], v[2:3], off offset:1024 nt
	global_load_dwordx2 v[84:85], v[2:3], off offset:1536 nt
	global_load_dwordx2 v[82:83], v[2:3], off offset:2048 nt
	global_load_dwordx2 v[80:81], v[2:3], off offset:2560 nt
	global_load_dwordx2 v[78:79], v[2:3], off offset:3072 nt
	global_load_dwordx2 v[76:77], v[2:3], off offset:3584 nt
	v_lshl_add_u64 v[2:3], v[8:9], 0, s[6:7]
	v_lshl_add_u64 v[2:3], v[2:3], 0, v[6:7]
	s_lshl_b64 s[6:7], s[22:23], 12
	global_load_dwordx2 v[72:73], v[2:3], off nt
	global_load_dwordx2 v[70:71], v[2:3], off offset:512 nt
	global_load_dwordx2 v[68:69], v[2:3], off offset:1024 nt
	global_load_dwordx2 v[66:67], v[2:3], off offset:1536 nt
	global_load_dwordx2 v[64:65], v[2:3], off offset:2048 nt
	global_load_dwordx2 v[62:63], v[2:3], off offset:2560 nt
	global_load_dwordx2 v[60:61], v[2:3], off offset:3072 nt
	global_load_dwordx2 v[58:59], v[2:3], off offset:3584 nt
	v_lshl_add_u64 v[2:3], v[8:9], 0, s[6:7]
	v_lshl_add_u64 v[2:3], v[2:3], 0, v[6:7]
	s_lshl_b64 s[6:7], s[18:19], 12
	global_load_dwordx2 v[56:57], v[2:3], off nt
	global_load_dwordx2 v[54:55], v[2:3], off offset:512 nt
	global_load_dwordx2 v[52:53], v[2:3], off offset:1024 nt
	global_load_dwordx2 v[50:51], v[2:3], off offset:1536 nt
	global_load_dwordx2 v[48:49], v[2:3], off offset:2048 nt
	global_load_dwordx2 v[46:47], v[2:3], off offset:2560 nt
	global_load_dwordx2 v[44:45], v[2:3], off offset:3072 nt
	global_load_dwordx2 v[42:43], v[2:3], off offset:3584 nt
	v_lshl_add_u64 v[2:3], v[8:9], 0, s[6:7]
	v_lshl_add_u64 v[2:3], v[2:3], 0, v[6:7]
	s_lshl_b64 s[6:7], s[14:15], 12
	global_load_dwordx2 v[40:41], v[2:3], off nt
	global_load_dwordx2 v[38:39], v[2:3], off offset:512 nt
	global_load_dwordx2 v[36:37], v[2:3], off offset:1024 nt
	global_load_dwordx2 v[34:35], v[2:3], off offset:1536 nt
	global_load_dwordx2 v[32:33], v[2:3], off offset:2048 nt
	global_load_dwordx2 v[30:31], v[2:3], off offset:2560 nt
	global_load_dwordx2 v[28:29], v[2:3], off offset:3072 nt
	global_load_dwordx2 v[26:27], v[2:3], off offset:3584 nt
	v_lshl_add_u64 v[2:3], v[8:9], 0, s[6:7]
	v_lshl_add_u64 v[2:3], v[2:3], 0, v[6:7]
	global_load_dwordx2 v[24:25], v[2:3], off nt
	global_load_dwordx2 v[22:23], v[2:3], off offset:512 nt
	global_load_dwordx2 v[20:21], v[2:3], off offset:1024 nt
	global_load_dwordx2 v[18:19], v[2:3], off offset:1536 nt
	global_load_dwordx2 v[16:17], v[2:3], off offset:2048 nt
	global_load_dwordx2 v[14:15], v[2:3], off offset:2560 nt
	global_load_dwordx2 v[12:13], v[2:3], off offset:3072 nt
	global_load_dwordx2 v[10:11], v[2:3], off offset:3584 nt
	s_waitcnt vmcnt(62)
; #define GAS __attribute__((address_space(1)))
; #define LAS __attribute__((address_space(3)))
; #define NR_LOAD(dst, k_) do { const GAS v2u* xr_ = (const GAS v2u*)(X + (size_t)(nw + 2048 * (k_)) * D) + F.lane; \
;         _Pragma("unroll") for (int j = 0; j < 8; ++j) dst[j] = __builtin_nontemporal_load(xr_ + 64 * j); } while (0)
; __device__ __forceinline__ void norm_mod_phase2(const Args& a, Frame& F, const float* gain, const float* modl, int sh_off, int sc_off, int nrows, const float* slab_gate) {
;     ...
;     NR_LOAD(r0, 0); NR_LOAD(r1, 1); NR_LOAD(r2, 2); NR_LOAD(r3, 3); NR_LOAD(r4, 4); NR_LOAD(r5, 5); NR_LOAD(r6, 6); NR_LOAD(r7, 7);
;     { const GAS f32x4* g4 = (const GAS f32x4*)gain;
;       for (int q = F.tid; q < 5 * D / 4; q += NWAVES * 64) { const int bq = q >> 9, cq = q & 511; const GAS f32x4* mb4 = (const GAS f32x4*)(modl + (size_t)bq * MOD_LD);
;           ((LAS f32x4*)CA)[q] = g4[cq] * (mb4[sc_off / 4 + cq] + 1.0f); ((LAS f32x4*)CB)[q] = mb4[sh_off / 4 + cq]; } }
	v_lshl_add_u32 v184, v142, 4, 0
	v_add_u32_e32 v185, 0xa000, v184
	v_add_f32_e32 v210, 1.0, v210
	v_add_f32_e32 v211, 1.0, v211
	v_add_f32_e32 v208, 1.0, v208
	v_add_f32_e32 v209, 1.0, v209
	v_mul_f32_e32 v210, v194, v210
	v_mul_f32_e32 v211, v195, v211
	v_mul_f32_e32 v208, v192, v208
	v_mul_f32_e32 v209, v193, v209
	ds_write_b128 v184, v[208:211]
	ds_write_b128 v185, v[228:231]
	v_add_f32_e32 v214, 1.0, v214
	v_add_f32_e32 v215, 1.0, v215
	v_add_f32_e32 v212, 1.0, v212
	v_add_f32_e32 v213, 1.0, v213
	v_mul_f32_e32 v214, v194, v214
	v_mul_f32_e32 v215, v195, v215
	v_mul_f32_e32 v212, v192, v212
	v_mul_f32_e32 v213, v193, v213
	ds_write_b128 v184, v[212:215] offset:8192
	ds_write_b128 v185, v[232:235] offset:8192
	v_add_f32_e32 v218, 1.0, v218
	v_add_f32_e32 v219, 1.0, v219
	v_add_f32_e32 v216, 1.0, v216
	v_add_f32_e32 v217, 1.0, v217
	v_mul_f32_e32 v218, v194, v218
	v_mul_f32_e32 v219, v195, v219
	v_mul_f32_e32 v216, v192, v216
	v_mul_f32_e32 v217, v193, v217
	ds_write_b128 v184, v[216:219] offset:16384
	ds_write_b128 v185, v[236:239] offset:16384
	v_add_f32_e32 v222, 1.0, v222
	v_add_f32_e32 v223, 1.0, v223
	v_add_f32_e32 v220, 1.0, v220
	v_add_f32_e32 v221, 1.0, v221
	v_mul_f32_e32 v222, v194, v222
	v_mul_f32_e32 v223, v195, v223
	v_mul_f32_e32 v220, v192, v220
	v_mul_f32_e32 v221, v193, v221
	ds_write_b128 v184, v[220:223] offset:24576
	ds_write_b128 v185, v[240:243] offset:24576
	v_add_f32_e32 v226, 1.0, v226
	v_add_f32_e32 v227, 1.0, v227
	v_add_f32_e32 v224, 1.0, v224
	v_add_f32_e32 v225, 1.0, v225
	v_mul_f32_e32 v226, v194, v226
	v_mul_f32_e32 v227, v195, v227
	v_mul_f32_e32 v224, v192, v224
	v_mul_f32_e32 v225, v193, v225
	ds_write_b128 v184, v[224:227] offset:32768
	ds_write_b128 v185, v[244:247] offset:32768
	s_waitcnt vmcnt(62)
	v_cvt_f32_f16_sdwa v153, v140 dst_sel:DWORD dst_unused:UNUSED_PAD src0_sel:WORD_1
	v_cvt_f32_f16_sdwa v149, v138 dst_sel:DWORD dst_unused:UNUSED_PAD src0_sel:WORD_1
	v_cvt_f32_f16_e32 v152, v140
	v_cvt_f32_f16_sdwa v155, v141 dst_sel:DWORD dst_unused:UNUSED_PAD src0_sel:WORD_1
	v_cvt_f32_f16_e32 v148, v138
	v_cvt_f32_f16_sdwa v151, v139 dst_sel:DWORD dst_unused:UNUSED_PAD src0_sel:WORD_1
	v_cvt_f32_f16_e32 v154, v141
	v_cvt_f32_f16_e32 v150, v139
	s_waitcnt vmcnt(61)
	v_cvt_f32_f16_sdwa v139, v134 dst_sel:DWORD dst_unused:UNUSED_PAD src0_sel:WORD_1
	v_cvt_f32_f16_sdwa v141, v135 dst_sel:DWORD dst_unused:UNUSED_PAD src0_sel:WORD_1
	s_mov_b64 s[6:7], 0x8c00000
	v_mov_b32_e32 v74, v153
	v_mov_b32_e32 v75, v149
	v_cvt_f32_f16_e32 v138, v134
	v_cvt_f32_f16_e32 v140, v135
	v_lshl_add_u64 v[2:3], v[136:137], 0, s[6:7]
	v_mov_b32_e32 v4, v152
	v_mov_b32_e32 v5, v148
	v_mul_f32_e32 v74, v74, v74
	v_mul_f32_e32 v75, v75, v75
	v_mov_b32_e32 v136, v155
	v_mov_b32_e32 v137, v151
	v_fma_f32 v4, v4, v4, v74
	v_fma_f32 v5, v5, v5, v75
	v_mov_b32_e32 v74, v154
	v_mov_b32_e32 v75, v150
	v_mul_f32_e32 v136, v136, v136
	v_mul_f32_e32 v137, v137, v137
	v_mov_b32_e32 v134, v139
	v_fma_f32 v74, v74, v74, v136
	v_fma_f32 v75, v75, v75, v137
	v_mov_b32_e32 v135, v141
	s_waitcnt vmcnt(60)
	v_cvt_f32_f16_sdwa v143, v132 dst_sel:DWORD dst_unused:UNUSED_PAD src0_sel:WORD_1
	v_add_f32_e32 v4, v4, v74
	v_add_f32_e32 v5, v5, v75
	v_mov_b32_e32 v74, v138
	v_mov_b32_e32 v75, v140
	v_mul_f32_e32 v134, v134, v134
	v_mul_f32_e32 v135, v135, v135
	v_cvt_f32_f16_e32 v142, v132
	v_cvt_f32_f16_sdwa v145, v133 dst_sel:DWORD dst_unused:UNUSED_PAD src0_sel:WORD_1
	v_fma_f32 v74, v74, v74, v134
	v_fma_f32 v75, v75, v75, v135
	v_cvt_f32_f16_e32 v144, v133
	s_waitcnt vmcnt(59)
	v_cvt_f32_f16_sdwa v133, v130 dst_sel:DWORD dst_unused:UNUSED_PAD src0_sel:WORD_1
	v_cvt_f32_f16_e32 v132, v130
	v_cvt_f32_f16_sdwa v135, v131 dst_sel:DWORD dst_unused:UNUSED_PAD src0_sel:WORD_1
	v_cvt_f32_f16_e32 v134, v131
	v_mul_f32_e32 v0, v143, v143
	v_fma_f32 v136, v142, v142, v0
	v_fma_f32 v137, v143, v143, v0
	v_mul_f32_e32 v0, v145, v145
	v_pk_add_f32 v[4:5], v[4:5], v[4:5] op_sel:[0,1] op_sel_hi:[1,0]
	v_pk_add_f32 v[74:75], v[74:75], v[74:75] op_sel:[0,1] op_sel_hi:[1,0]
	v_fma_f32 v156, v144, v144, v0
	v_fma_f32 v157, v145, v145, v0
	v_mul_f32_e32 v130, v132, v132
	v_mul_f32_e32 v131, v133, v133
	v_mul_f32_e32 v158, v134, v134
	v_mul_f32_e32 v159, v135, v135
	v_mov_b32_e32 v5, v130
	v_mov_b32_e32 v75, v131
	v_mov_b32_e32 v137, v158
	v_mov_b32_e32 v157, v159
	v_add_f32_e32 v4, v4, v74
	v_add_f32_e32 v5, v5, v75
	v_add_f32_e32 v74, v136, v156
	v_add_f32_e32 v75, v137, v157
	s_waitcnt vmcnt(58)
	v_cvt_f32_f16_sdwa v131, v128 dst_sel:DWORD dst_unused:UNUSED_PAD src0_sel:WORD_1
	v_cvt_f32_f16_sdwa v137, v129 dst_sel:DWORD dst_unused:UNUSED_PAD src0_sel:WORD_1
	v_cvt_f32_f16_e32 v130, v128
	v_cvt_f32_f16_e32 v136, v129
	v_add_f32_e32 v4, v4, v74
	v_add_f32_e32 v5, v5, v75
	v_mov_b32_e32 v74, v131
	v_mov_b32_e32 v75, v137
	v_add_f32_e32 v156, v4, v5
	v_add_f32_e32 v157, v5, v4
	v_mov_b32_e32 v4, v130
	v_mov_b32_e32 v5, v136
	v_mul_f32_e32 v74, v74, v74
	v_mul_f32_e32 v75, v75, v75
	s_waitcnt vmcnt(57)
	v_cvt_f32_f16_sdwa v129, v127 dst_sel:DWORD dst_unused:UNUSED_PAD src0_sel:WORD_1
	v_fma_f32 v4, v4, v4, v74
	v_fma_f32 v5, v5, v5, v75
	v_cvt_f32_f16_e32 v128, v127
	v_add_f32_e32 v158, v4, v5
	v_add_f32_e32 v159, v5, v4
	v_cvt_f32_f16_sdwa v5, v126 dst_sel:DWORD dst_unused:UNUSED_PAD src0_sel:WORD_1
	v_cvt_f32_f16_e32 v4, v126
	s_waitcnt vmcnt(56)
	v_cvt_f32_f16_sdwa v75, v124 dst_sel:DWORD dst_unused:UNUSED_PAD src0_sel:WORD_1
	v_cvt_f32_f16_e32 v74, v124
	v_cvt_f32_f16_sdwa v127, v125 dst_sel:DWORD dst_unused:UNUSED_PAD src0_sel:WORD_1
	v_cvt_f32_f16_e32 v126, v125
	v_mul_f32_e32 v0, v5, v5
	v_fma_f32 v160, v4, v4, v0
	v_fma_f32 v161, v5, v5, v0
	v_mul_f32_e32 v0, v129, v129
	v_fma_f32 v162, v128, v128, v0
	v_fma_f32 v163, v129, v129, v0
	v_mul_f32_e32 v124, v74, v74
	v_mul_f32_e32 v125, v75, v75
	v_mul_f32_e32 v164, v126, v126
	v_mul_f32_e32 v165, v127, v127
	v_mov_b32_e32 v157, v124
	v_mov_b32_e32 v159, v125
	v_mov_b32_e32 v161, v164
	v_mov_b32_e32 v163, v165
	v_add_f32_e32 v124, v156, v158
	v_add_f32_e32 v125, v157, v159
	v_add_f32_e32 v156, v160, v162
	v_add_f32_e32 v157, v161, v163
	s_waitcnt lgkmcnt(0)
	s_barrier
; #define GAS __attribute__((address_space(1)))
; #define LAS __attribute__((address_space(3)))
; #define NR_LOAD(dst, k_) do { const GAS v2u* xr_ = (const GAS v2u*)(X + (size_t)(nw + 2048 * (k_)) * D) + F.lane; \
;         _Pragma("unroll") for (int j = 0; j < 8; ++j) dst[j] = __builtin_nontemporal_load(xr_ + 64 * j); } while (0)
; __device__ __forceinline__ void norm_mod_phase2(const Args& a, Frame& F, const float* gain, const float* modl, int sh_off, int sc_off, int nrows, const float* slab_gate) {
;     ...
;     NR_LOAD(r0, 0); NR_LOAD(r1, 1); NR_LOAD(r2, 2); NR_LOAD(r3, 3); NR_LOAD(r4, 4); NR_LOAD(r5, 5); NR_LOAD(r6, 6); NR_LOAD(r7, 7);
;     { const GAS f32x4* g4 = (const GAS f32x4*)gain;
;       for (int q = F.tid; q < 5 * D / 4; q += NWAVES * 64) { const int bq = q >> 9, cq = q & 511; const GAS f32x4* mb4 = (const GAS f32x4*)(modl + (size_t)bq * MOD_LD);
;           ((LAS f32x4*)CA)[q] = g4[cq] * (mb4[sc_off / 4 + cq] + 1.0f); ((LAS f32x4*)CB)[q] = mb4[sh_off / 4 + cq]; } }
;     asm volatile("s_waitcnt lgkmcnt(0)" ::: "memory"); __builtin_amdgcn_s_barrier(); asm volatile("" ::: "memory");
;     NR_FINISH(r0, nw,            (nw) >> 12);
	v_add_f32_e32 v124, v124, v156
	v_add_f32_e32 v125, v125, v157
	s_lshl_b64 s[12:13], s[10:11], 11
	v_add_f32_e32 v0, v124, v125
	s_lshl_b64 s[48:49], s[78:79], 11
	s_lshl_b64 s[40:41], s[36:37], 11
	v_add_f32_dpp v0, v0, v0 quad_perm:[1,0,3,2] row_mask:0xf bank_mask:0xf bound_ctrl:1
	s_lshl_b64 s[34:35], s[30:31], 11
	s_lshl_b64 s[28:29], s[26:27], 11
	v_add_f32_dpp v0, v0, v0 quad_perm:[2,3,0,1] row_mask:0xf bank_mask:0xf bound_ctrl:1
	s_lshl_b64 s[24:25], s[22:23], 11
	s_lshl_b64 s[20:21], s[18:19], 11
	v_add_f32_dpp v0, v0, v0 row_half_mirror row_mask:0xf bank_mask:0xf bound_ctrl:1
	s_lshl_b64 s[16:17], s[14:15], 11
	s_nop 0
	v_add_f32_dpp v0, v0, v0 row_mirror row_mask:0xf bank_mask:0xf bound_ctrl:1
	s_nop 0
	v_readlane_b32 s8, v0, 16
	v_readlane_b32 s9, v0, 48
	v_readlane_b32 s6, v0, 0
	v_readlane_b32 s7, v0, 32
	v_mov_b32_e32 v124, s8
	v_mov_b32_e32 v125, s9
	v_add_f32_e32 v124, s6, v124
	v_add_f32_e32 v125, s7, v125
	s_nop 0
	v_add_f32_e32 v0, v124, v125
	v_fmamk_f32 v0, v0, 0x3a000000, v252
	v_cmp_gt_f32_e32 vcc, s55, v0
	v_mul_f32_e32 v7, 0x4f800000, v0
	s_nop 0
	v_cndmask_b32_e32 v0, v0, v7, vcc
	v_sqrt_f32_e32 v7, v0
	s_nop 0
	v_add_u32_e32 v124, -1, v7
	v_fma_f32 v125, -v124, v7, v0
	v_cmp_ge_f32_e64 s[8:9], 0, v125
	v_add_u32_e32 v125, 1, v7
	s_nop 0
	v_cndmask_b32_e64 v124, v7, v124, s[8:9]
	v_fma_f32 v7, -v125, v7, v0
	v_cmp_lt_f32_e64 s[8:9], 0, v7
	s_nop 1
	v_cndmask_b32_e64 v7, v124, v125, s[8:9]
	v_mul_f32_e32 v124, 0x37800000, v7
	v_cndmask_b32_e32 v7, v7, v124, vcc
	v_cmp_class_f32_e32 vcc, v0, v253
	s_nop 1
	v_cndmask_b32_e32 v0, v7, v0, vcc
	v_div_scale_f32 v7, s[6:7], v0, v0, 1.0
	v_rcp_f32_e32 v124, v7
	s_lshl_b32 s6, s10, 1
	s_and_b32 s6, s6, 0xffffe000
	s_add_i32 s6, s6, 0
	v_fma_f32 v125, -v7, v124, 1.0
	v_fmac_f32_e32 v124, v125, v124
	v_div_scale_f32 v125, vcc, 1.0, v0, 1.0
	v_mul_f32_e32 v146, v125, v124
	v_fma_f32 v156, -v7, v146, v125
	v_fmac_f32_e32 v146, v156, v124
	v_fma_f32 v7, -v7, v146, v125
	v_div_fmas_f32 v7, v7, v124, v146
	v_div_fixup_f32 v146, v7, v0, 1.0
	v_lshlrev_b32_e32 v0, 4, v147
	v_add_u32_e32 v164, s6, v0
	v_mul_f32_e32 v160, v152, v146
	v_mul_f32_e32 v161, v153, v146
	v_mul_f32_e32 v162, v154, v146
	v_mul_f32_e32 v163, v155, v146
	ds_read_b128 v[152:155], v164
	ds_read_b128 v[156:159], v164 offset:40960
	v_lshl_add_u64 v[124:125], s[12:13], 1, v[2:3]
	v_mov_b32_e32 v7, v1
	v_lshl_add_u64 v[124:125], v[124:125], 0, v[6:7]
	v_mul_f32_e32 v4, v4, v146
	v_mul_f32_e32 v5, v5, v146
	s_waitcnt lgkmcnt(0)
	v_fma_f32 v154, v154, v162, v158
	v_fma_f32 v155, v155, v163, v159
	v_fma_f32 v152, v152, v160, v156
	v_fma_f32 v153, v153, v161, v157
	v_mul_f32_e32 v156, v148, v146
	v_mul_f32_e32 v157, v149, v146
	v_cvt_pk_bf16_f32 v152, v152, v153
	v_cvt_pk_bf16_f32 v153, v154, v155
	global_store_dwordx2 v[124:125], v[152:153], off
	v_mul_f32_e32 v158, v150, v146
	v_mul_f32_e32 v159, v151, v146
	ds_read_b128 v[148:151], v164 offset:1024
	ds_read_b128 v[152:155], v164 offset:41984
	s_waitcnt lgkmcnt(0)
	v_fma_f32 v150, v150, v158, v154
	v_fma_f32 v151, v151, v159, v155
	v_fma_f32 v148, v148, v156, v152
	v_fma_f32 v149, v149, v157, v153
	v_mul_f32_e32 v152, v138, v146
	v_mul_f32_e32 v153, v139, v146
	v_cvt_pk_bf16_f32 v148, v148, v149
	v_cvt_pk_bf16_f32 v149, v150, v151
	global_store_dwordx2 v[124:125], v[148:149], off offset:512
	v_mul_f32_e32 v154, v140, v146
	v_mul_f32_e32 v155, v141, v146
	ds_read_b128 v[138:141], v164 offset:2048
	ds_read_b128 v[148:151], v164 offset:43008
	s_waitcnt lgkmcnt(0)
	v_fma_f32 v140, v140, v154, v150
	v_fma_f32 v141, v141, v155, v151
	v_fma_f32 v138, v138, v152, v148
	v_fma_f32 v139, v139, v153, v149
	v_mul_f32_e32 v148, v142, v146
	v_mul_f32_e32 v149, v143, v146
	v_cvt_pk_bf16_f32 v138, v138, v139
	v_cvt_pk_bf16_f32 v139, v140, v141
	global_store_dwordx2 v[124:125], v[138:139], off offset:1024
	v_mul_f32_e32 v150, v144, v146
	v_mul_f32_e32 v151, v145, v146
	ds_read_b128 v[138:141], v164 offset:3072
	ds_read_b128 v[142:145], v164 offset:44032
	s_waitcnt lgkmcnt(0)
	v_fma_f32 v140, v150, v140, v144
	v_fma_f32 v141, v151, v141, v145
	v_fma_f32 v138, v148, v138, v142
	v_fma_f32 v139, v149, v139, v143
	v_mul_f32_e32 v142, v132, v146
	v_mul_f32_e32 v143, v133, v146
	v_cvt_pk_bf16_f32 v138, v138, v139
	v_cvt_pk_bf16_f32 v139, v140, v141
	global_store_dwordx2 v[124:125], v[138:139], off offset:1536
	v_mul_f32_e32 v144, v134, v146
	v_mul_f32_e32 v145, v135, v146
	ds_read_b128 v[132:135], v164 offset:4096
	ds_read_b128 v[138:141], v164 offset:45056
	s_waitcnt lgkmcnt(0)
	v_fma_f32 v134, v144, v134, v140
	v_fma_f32 v135, v145, v135, v141
	v_fma_f32 v132, v142, v132, v138
	v_fma_f32 v133, v143, v133, v139
	v_mul_f32_e32 v138, v130, v146
	v_mul_f32_e32 v139, v131, v146
	v_cvt_pk_bf16_f32 v132, v132, v133
	v_cvt_pk_bf16_f32 v133, v134, v135
	global_store_dwordx2 v[124:125], v[132:133], off offset:2048
	v_mul_f32_e32 v140, v136, v146
	v_mul_f32_e32 v141, v137, v146
	ds_read_b128 v[130:133], v164 offset:5120
	ds_read_b128 v[134:137], v164 offset:46080
	s_waitcnt lgkmcnt(0)
	v_fma_f32 v132, v140, v132, v136
	v_fma_f32 v133, v141, v133, v137
	v_fma_f32 v130, v138, v130, v134
	v_fma_f32 v131, v139, v131, v135
	v_mul_f32_e32 v136, v128, v146
	v_mul_f32_e32 v137, v129, v146
	v_cvt_pk_bf16_f32 v130, v130, v131
	v_cvt_pk_bf16_f32 v131, v132, v133
	global_store_dwordx2 v[124:125], v[130:131], off offset:2560
	ds_read_b128 v[128:131], v164 offset:6144
	ds_read_b128 v[132:135], v164 offset:47104
	s_waitcnt vmcnt(61)
	v_cvt_f32_f16_sdwa v139, v123 dst_sel:DWORD dst_unused:UNUSED_PAD src0_sel:WORD_1
	v_cvt_f32_f16_e32 v138, v123
	s_waitcnt vmcnt(59)
; #define GAS __attribute__((address_space(1)))
; #define LAS __attribute__((address_space(3)))
; #define NR_LOAD(dst, k_) do { const GAS v2u* xr_ = (const GAS v2u*)(X + (size_t)(nw + 2048 * (k_)) * D) + F.lane; \
;         _Pragma("unroll") for (int j = 0; j < 8; ++j) dst[j] = __builtin_nontemporal_load(xr_ + 64 * j); } while (0)
; __device__ __forceinline__ void norm_mod_phase2(const Args& a, Frame& F, const float* gain, const float* modl, int sh_off, int sc_off, int nrows, const float* slab_gate) {
;     ...
;     NR_LOAD(r0, 0); NR_LOAD(r1, 1); NR_LOAD(r2, 2); NR_LOAD(r3, 3); NR_LOAD(r4, 4); NR_LOAD(r5, 5); NR_LOAD(r6, 6); NR_LOAD(r7, 7);
;     { const GAS f32x4* g4 = (const GAS f32x4*)gain;
;       for (int q = F.tid; q < 5 * D / 4; q += NWAVES * 64) { const int bq = q >> 9, cq = q & 511; const GAS f32x4* mb4 = (const GAS f32x4*)(modl + (size_t)bq * MOD_LD);
;           ((LAS f32x4*)CA)[q] = g4[cq] * (mb4[sc_off / 4 + cq] + 1.0f); ((LAS f32x4*)CB)[q] = mb4[sh_off / 4 + cq]; } }
;     asm volatile("s_waitcnt lgkmcnt(0)" ::: "memory"); __builtin_amdgcn_s_barrier(); asm volatile("" ::: "memory");
;     NR_FINISH(r0, nw,            (nw) >> 12);
;     NR_FINISH(r1, nw + 2048,     (nw + 2048) >> 12);
	v_cvt_f32_f16_sdwa v123, v118 dst_sel:DWORD dst_unused:UNUSED_PAD src0_sel:WORD_1
	s_waitcnt lgkmcnt(0)
	v_fma_f32 v130, v136, v130, v134
	v_fma_f32 v131, v137, v131, v135
	v_fma_f32 v4, v4, v128, v132
	v_fma_f32 v5, v5, v129, v133
	v_cvt_f32_f16_sdwa v137, v122 dst_sel:DWORD dst_unused:UNUSED_PAD src0_sel:WORD_1
	v_cvt_pk_bf16_f32 v4, v4, v5
	v_cvt_pk_bf16_f32 v5, v130, v131
	global_store_dwordx2 v[124:125], v[4:5], off offset:3072
	v_mul_f32_e32 v4, v74, v146
	v_mul_f32_e32 v5, v75, v146
	v_mul_f32_e32 v74, v126, v146
	v_mul_f32_e32 v75, v127, v146
	ds_read_b128 v[126:129], v164 offset:7168
	ds_read_b128 v[130:133], v164 offset:48128
	v_cvt_f32_f16_e32 v136, v122
	v_cvt_f32_f16_sdwa v135, v121 dst_sel:DWORD dst_unused:UNUSED_PAD src0_sel:WORD_1
	v_cvt_f32_f16_e32 v134, v121
	v_cvt_f32_f16_e32 v122, v118
	s_waitcnt lgkmcnt(0)
	v_fma_f32 v74, v74, v128, v132
	v_fma_f32 v75, v75, v129, v133
	v_cvt_f32_f16_sdwa v133, v120 dst_sel:DWORD dst_unused:UNUSED_PAD src0_sel:WORD_1
	v_fma_f32 v4, v4, v126, v130
	v_fma_f32 v5, v5, v127, v131
	v_cvt_f32_f16_e32 v132, v120
	v_cvt_pk_bf16_f32 v4, v4, v5
	v_cvt_pk_bf16_f32 v5, v74, v75
	global_store_dwordx2 v[124:125], v[4:5], off offset:3584
	v_cvt_f32_f16_sdwa v125, v119 dst_sel:DWORD dst_unused:UNUSED_PAD src0_sel:WORD_1
	s_waitcnt vmcnt(60)
	v_cvt_f32_f16_sdwa v127, v116 dst_sel:DWORD dst_unused:UNUSED_PAD src0_sel:WORD_1
	v_mov_b32_e32 v74, v137
	v_mov_b32_e32 v75, v133
	v_cvt_f32_f16_e32 v124, v119
	v_cvt_f32_f16_e32 v126, v116
	v_cvt_f32_f16_sdwa v129, v117 dst_sel:DWORD dst_unused:UNUSED_PAD src0_sel:WORD_1
	v_mov_b32_e32 v4, v136
	v_mov_b32_e32 v5, v132
	v_mul_f32_e32 v74, v74, v74
	v_mul_f32_e32 v75, v75, v75
	v_mov_b32_e32 v120, v139
	v_mov_b32_e32 v121, v135
	v_cvt_f32_f16_e32 v128, v117
	v_fma_f32 v4, v4, v4, v74
	v_fma_f32 v5, v5, v5, v75
	v_mov_b32_e32 v74, v138
	v_mov_b32_e32 v75, v134
	v_mul_f32_e32 v120, v120, v120
	v_mul_f32_e32 v121, v121, v121
	v_mov_b32_e32 v118, v123
	v_fma_f32 v74, v74, v74, v120
	v_fma_f32 v75, v75, v75, v121
	v_mov_b32_e32 v119, v125
	v_mul_f32_e32 v116, v127, v127
	v_add_f32_e32 v4, v4, v74
	v_add_f32_e32 v5, v5, v75
	v_mov_b32_e32 v74, v122
	v_mov_b32_e32 v75, v124
	v_mul_f32_e32 v118, v118, v118
	v_mul_f32_e32 v119, v119, v119
	v_fma_f32 v120, v126, v126, v116
	v_fma_f32 v121, v127, v127, v116
	v_mul_f32_e32 v116, v129, v129
	v_fma_f32 v74, v74, v74, v118
	v_fma_f32 v75, v75, v75, v119
	v_fma_f32 v130, v128, v128, v116
	v_fma_f32 v131, v129, v129, v116
	s_waitcnt vmcnt(59)
	v_cvt_f32_f16_sdwa v117, v114 dst_sel:DWORD dst_unused:UNUSED_PAD src0_sel:WORD_1
	v_cvt_f32_f16_e32 v116, v114
	v_cvt_f32_f16_sdwa v119, v115 dst_sel:DWORD dst_unused:UNUSED_PAD src0_sel:WORD_1
	v_cvt_f32_f16_e32 v118, v115
	v_pk_add_f32 v[4:5], v[4:5], v[4:5] op_sel:[0,1] op_sel_hi:[1,0]
	v_pk_add_f32 v[74:75], v[74:75], v[74:75] op_sel:[0,1] op_sel_hi:[1,0]
	v_mul_f32_e32 v114, v116, v116
	v_mul_f32_e32 v115, v117, v117
	v_mul_f32_e32 v140, v118, v118
	v_mul_f32_e32 v141, v119, v119
	v_mov_b32_e32 v5, v114
	v_mov_b32_e32 v75, v115
	v_mov_b32_e32 v121, v140
	v_mov_b32_e32 v131, v141
	v_add_f32_e32 v4, v4, v74
	v_add_f32_e32 v5, v5, v75
	v_add_f32_e32 v74, v120, v130
	v_add_f32_e32 v75, v121, v131
	s_waitcnt vmcnt(58)
	v_cvt_f32_f16_sdwa v115, v112 dst_sel:DWORD dst_unused:UNUSED_PAD src0_sel:WORD_1
	v_cvt_f32_f16_sdwa v121, v113 dst_sel:DWORD dst_unused:UNUSED_PAD src0_sel:WORD_1
	v_cvt_f32_f16_e32 v114, v112
	v_cvt_f32_f16_e32 v120, v113
	v_add_f32_e32 v4, v4, v74
	v_add_f32_e32 v5, v5, v75
	v_mov_b32_e32 v74, v115
	v_mov_b32_e32 v75, v121
	v_add_f32_e32 v130, v4, v5
	v_add_f32_e32 v131, v5, v4
	v_mov_b32_e32 v4, v114
	v_mov_b32_e32 v5, v120
	v_mul_f32_e32 v74, v74, v74
	v_mul_f32_e32 v75, v75, v75
	s_waitcnt vmcnt(57)
	v_cvt_f32_f16_sdwa v113, v111 dst_sel:DWORD dst_unused:UNUSED_PAD src0_sel:WORD_1
	v_fma_f32 v4, v4, v4, v74
	v_fma_f32 v5, v5, v5, v75
	v_cvt_f32_f16_e32 v112, v111
	v_add_f32_e32 v140, v4, v5
	v_add_f32_e32 v141, v5, v4
	v_cvt_f32_f16_sdwa v5, v110 dst_sel:DWORD dst_unused:UNUSED_PAD src0_sel:WORD_1
	v_cvt_f32_f16_e32 v4, v110
	s_waitcnt vmcnt(56)
	v_cvt_f32_f16_sdwa v111, v109 dst_sel:DWORD dst_unused:UNUSED_PAD src0_sel:WORD_1
	v_cvt_f32_f16_e32 v110, v109
	v_mul_f32_e32 v74, v5, v5
	v_fma_f32 v142, v4, v4, v74
	v_fma_f32 v143, v5, v5, v74
	v_mul_f32_e32 v74, v113, v113
	v_fma_f32 v144, v112, v112, v74
	v_fma_f32 v145, v113, v113, v74
	v_cvt_f32_f16_sdwa v75, v108 dst_sel:DWORD dst_unused:UNUSED_PAD src0_sel:WORD_1
	v_cvt_f32_f16_e32 v74, v108
	v_mul_f32_e32 v148, v110, v110
	v_mul_f32_e32 v149, v111, v111
	v_mul_f32_e32 v108, v74, v74
	v_mul_f32_e32 v109, v75, v75
	s_nop 0
	v_mov_b32_e32 v131, v108
	v_mov_b32_e32 v141, v109
	v_mov_b32_e32 v143, v148
	v_mov_b32_e32 v145, v149
	v_add_f32_e32 v108, v130, v140
	v_add_f32_e32 v109, v131, v141
	v_add_f32_e32 v130, v142, v144
	v_add_f32_e32 v131, v143, v145
	s_nop 0
	v_add_f32_e32 v108, v108, v130
	v_add_f32_e32 v109, v109, v131
	s_nop 0
	v_add_f32_e32 v108, v108, v109
	s_nop 1
	v_add_f32_dpp v108, v108, v108 quad_perm:[1,0,3,2] row_mask:0xf bank_mask:0xf bound_ctrl:1
	s_nop 1
	v_add_f32_dpp v108, v108, v108 quad_perm:[2,3,0,1] row_mask:0xf bank_mask:0xf bound_ctrl:1
	s_nop 1
	v_add_f32_dpp v108, v108, v108 row_half_mirror row_mask:0xf bank_mask:0xf bound_ctrl:1
	s_nop 1
	v_add_f32_dpp v108, v108, v108 row_mirror row_mask:0xf bank_mask:0xf bound_ctrl:1
	s_nop 0
	v_readlane_b32 s8, v108, 16
	v_readlane_b32 s9, v108, 48
	v_readlane_b32 s6, v108, 0
	v_readlane_b32 s7, v108, 32
	v_mov_b32_e32 v108, s8
	v_mov_b32_e32 v109, s9
	v_add_f32_e32 v108, s6, v108
	v_add_f32_e32 v109, s7, v109
	s_nop 0
	v_add_f32_e32 v108, v108, v109
; #define GAS __attribute__((address_space(1)))
; #define LAS __attribute__((address_space(3)))
; #define NR_LOAD(dst, k_) do { const GAS v2u* xr_ = (const GAS v2u*)(X + (size_t)(nw + 2048 * (k_)) * D) + F.lane; \
;         _Pragma("unroll") for (int j = 0; j < 8; ++j) dst[j] = __builtin_nontemporal_load(xr_ + 64 * j); } while (0)
; __device__ __forceinline__ void norm_mod_phase2(const Args& a, Frame& F, const float* gain, const float* modl, int sh_off, int sc_off, int nrows, const float* slab_gate) {
;     ...
;     NR_LOAD(r0, 0); NR_LOAD(r1, 1); NR_LOAD(r2, 2); NR_LOAD(r3, 3); NR_LOAD(r4, 4); NR_LOAD(r5, 5); NR_LOAD(r6, 6); NR_LOAD(r7, 7);
;     { const GAS f32x4* g4 = (const GAS f32x4*)gain;
;       for (int q = F.tid; q < 5 * D / 4; q += NWAVES * 64) { const int bq = q >> 9, cq = q & 511; const GAS f32x4* mb4 = (const GAS f32x4*)(modl + (size_t)bq * MOD_LD);
;           ((LAS f32x4*)CA)[q] = g4[cq] * (mb4[sc_off / 4 + cq] + 1.0f); ((LAS f32x4*)CB)[q] = mb4[sh_off / 4 + cq]; } }
;     asm volatile("s_waitcnt lgkmcnt(0)" ::: "memory"); __builtin_amdgcn_s_barrier(); asm volatile("" ::: "memory");
;     NR_FINISH(r0, nw,            (nw) >> 12);
;     NR_FINISH(r1, nw + 2048,     (nw + 2048) >> 12);
	v_fmamk_f32 v108, v108, 0x3a000000, v252
	v_cmp_gt_f32_e32 vcc, s55, v108
	v_mul_f32_e32 v109, 0x4f800000, v108
	s_nop 0
	v_cndmask_b32_e32 v108, v108, v109, vcc
	v_sqrt_f32_e32 v109, v108
	s_nop 0
	v_add_u32_e32 v130, -1, v109
	v_fma_f32 v131, -v130, v109, v108
	v_cmp_ge_f32_e64 s[8:9], 0, v131
	v_add_u32_e32 v131, 1, v109
	s_nop 0
	v_cndmask_b32_e64 v130, v109, v130, s[8:9]
	v_fma_f32 v109, -v131, v109, v108
	v_cmp_lt_f32_e64 s[8:9], 0, v109
	s_nop 1
	v_cndmask_b32_e64 v109, v130, v131, s[8:9]
	v_mul_f32_e32 v130, 0x37800000, v109
	v_cndmask_b32_e32 v109, v109, v130, vcc
	v_cmp_class_f32_e32 vcc, v108, v253
	s_nop 1
	v_cndmask_b32_e32 v108, v109, v108, vcc
	v_div_scale_f32 v109, s[6:7], v108, v108, 1.0
	v_rcp_f32_e32 v130, v109
	s_lshl_b32 s6, s78, 1
	s_and_b32 s6, s6, 0xffffe000
	s_add_i32 s6, s6, 0
	v_fma_f32 v131, -v109, v130, 1.0
	v_fmac_f32_e32 v130, v131, v130
	v_div_scale_f32 v131, vcc, 1.0, v108, 1.0
	v_mul_f32_e32 v140, v131, v130
	v_fma_f32 v141, -v109, v140, v131
	v_fmac_f32_e32 v140, v141, v130
	v_fma_f32 v109, -v109, v140, v131
	v_div_fmas_f32 v109, v109, v130, v140
	v_div_fixup_f32 v130, v109, v108, 1.0
	v_mul_f32_e32 v144, v136, v130
	v_mul_f32_e32 v145, v137, v130
	v_mul_f32_e32 v148, v138, v130
	v_mul_f32_e32 v149, v139, v130
	v_add_u32_e32 v131, s6, v0
	ds_read_b128 v[136:139], v131
	ds_read_b128 v[140:143], v131 offset:40960
	v_lshl_add_u64 v[108:109], s[48:49], 1, v[2:3]
	v_lshl_add_u64 v[108:109], v[108:109], 0, v[6:7]
	v_mul_f32_e32 v4, v4, v130
	v_mul_f32_e32 v5, v5, v130
	s_waitcnt lgkmcnt(0)
	v_fma_f32 v138, v138, v148, v142
	v_fma_f32 v139, v139, v149, v143
	v_fma_f32 v136, v136, v144, v140
	v_fma_f32 v137, v137, v145, v141
	v_mul_f32_e32 v140, v132, v130
	v_mul_f32_e32 v141, v133, v130
	v_cvt_pk_bf16_f32 v136, v136, v137
	v_cvt_pk_bf16_f32 v137, v138, v139
	global_store_dwordx2 v[108:109], v[136:137], off
	v_mul_f32_e32 v142, v134, v130
	v_mul_f32_e32 v143, v135, v130
	ds_read_b128 v[132:135], v131 offset:1024
	ds_read_b128 v[136:139], v131 offset:41984
	s_waitcnt lgkmcnt(0)
	v_fma_f32 v134, v134, v142, v138
	v_fma_f32 v135, v135, v143, v139
	v_fma_f32 v132, v132, v140, v136
	v_fma_f32 v133, v133, v141, v137
	v_mul_f32_e32 v136, v122, v130
	v_mul_f32_e32 v137, v123, v130
	v_cvt_pk_bf16_f32 v132, v132, v133
	v_cvt_pk_bf16_f32 v133, v134, v135
	global_store_dwordx2 v[108:109], v[132:133], off offset:512
	v_mul_f32_e32 v138, v124, v130
	v_mul_f32_e32 v139, v125, v130
	ds_read_b128 v[122:125], v131 offset:2048
	ds_read_b128 v[132:135], v131 offset:43008
	s_waitcnt lgkmcnt(0)
	v_fma_f32 v124, v124, v138, v134
	v_fma_f32 v125, v125, v139, v135
	v_fma_f32 v122, v122, v136, v132
	v_fma_f32 v123, v123, v137, v133
	v_mul_f32_e32 v132, v126, v130
	v_mul_f32_e32 v133, v127, v130
	v_cvt_pk_bf16_f32 v122, v122, v123
	v_cvt_pk_bf16_f32 v123, v124, v125
	global_store_dwordx2 v[108:109], v[122:123], off offset:1024
	v_mul_f32_e32 v134, v128, v130
	v_mul_f32_e32 v135, v129, v130
	ds_read_b128 v[122:125], v131 offset:3072
	ds_read_b128 v[126:129], v131 offset:44032
	s_waitcnt lgkmcnt(0)
	v_fma_f32 v124, v134, v124, v128
	v_fma_f32 v125, v135, v125, v129
	v_fma_f32 v122, v132, v122, v126
	v_fma_f32 v123, v133, v123, v127
	v_mul_f32_e32 v126, v116, v130
	v_mul_f32_e32 v127, v117, v130
	v_cvt_pk_bf16_f32 v122, v122, v123
	v_cvt_pk_bf16_f32 v123, v124, v125
	global_store_dwordx2 v[108:109], v[122:123], off offset:1536
	v_mul_f32_e32 v128, v118, v130
	v_mul_f32_e32 v129, v119, v130
	ds_read_b128 v[116:119], v131 offset:4096
	ds_read_b128 v[122:125], v131 offset:45056
	s_waitcnt lgkmcnt(0)
	v_fma_f32 v118, v128, v118, v124
	v_fma_f32 v119, v129, v119, v125
	v_fma_f32 v116, v126, v116, v122
	v_fma_f32 v117, v127, v117, v123
	v_mul_f32_e32 v122, v114, v130
	v_mul_f32_e32 v123, v115, v130
	v_cvt_pk_bf16_f32 v116, v116, v117
	v_cvt_pk_bf16_f32 v117, v118, v119
	global_store_dwordx2 v[108:109], v[116:117], off offset:2048
	v_mul_f32_e32 v124, v120, v130
	v_mul_f32_e32 v125, v121, v130
	ds_read_b128 v[114:117], v131 offset:5120
	ds_read_b128 v[118:121], v131 offset:46080
	s_waitcnt lgkmcnt(0)
	v_fma_f32 v116, v124, v116, v120
	v_fma_f32 v117, v125, v117, v121
	v_fma_f32 v114, v122, v114, v118
	v_fma_f32 v115, v123, v115, v119
	v_mul_f32_e32 v120, v112, v130
	v_mul_f32_e32 v121, v113, v130
	v_cvt_pk_bf16_f32 v114, v114, v115
	v_cvt_pk_bf16_f32 v115, v116, v117
	global_store_dwordx2 v[108:109], v[114:115], off offset:2560
	ds_read_b128 v[112:115], v131 offset:6144
	ds_read_b128 v[116:119], v131 offset:47104
	s_waitcnt vmcnt(61)
	v_cvt_f32_f16_sdwa v123, v107 dst_sel:DWORD dst_unused:UNUSED_PAD src0_sel:WORD_1
	v_cvt_f32_f16_e32 v122, v107
	s_waitcnt vmcnt(59)
	v_cvt_f32_f16_sdwa v107, v102 dst_sel:DWORD dst_unused:UNUSED_PAD src0_sel:WORD_1
	s_waitcnt lgkmcnt(0)
	v_fma_f32 v114, v120, v114, v118
	v_fma_f32 v115, v121, v115, v119
	v_fma_f32 v4, v4, v112, v116
	v_fma_f32 v5, v5, v113, v117
	v_cvt_f32_f16_sdwa v121, v106 dst_sel:DWORD dst_unused:UNUSED_PAD src0_sel:WORD_1
	v_cvt_pk_bf16_f32 v4, v4, v5
	v_cvt_pk_bf16_f32 v5, v114, v115
	global_store_dwordx2 v[108:109], v[4:5], off offset:3072
	v_mul_f32_e32 v4, v74, v130
	v_mul_f32_e32 v5, v75, v130
	v_mul_f32_e32 v74, v110, v130
	v_mul_f32_e32 v75, v111, v130
	ds_read_b128 v[110:113], v131 offset:7168
	ds_read_b128 v[114:117], v131 offset:48128
	v_cvt_f32_f16_e32 v120, v106
	v_cvt_f32_f16_sdwa v119, v105 dst_sel:DWORD dst_unused:UNUSED_PAD src0_sel:WORD_1
	v_cvt_f32_f16_e32 v118, v105
	v_cvt_f32_f16_e32 v106, v102
	s_waitcnt lgkmcnt(0)
; #define GAS __attribute__((address_space(1)))
; #define LAS __attribute__((address_space(3)))
; #define NR_LOAD(dst, k_) do { const GAS v2u* xr_ = (const GAS v2u*)(X + (size_t)(nw + 2048 * (k_)) * D) + F.lane; \
;         _Pragma("unroll") for (int j = 0; j < 8; ++j) dst[j] = __builtin_nontemporal_load(xr_ + 64 * j); } while (0)
; __device__ __forceinline__ void norm_mod_phase2(const Args& a, Frame& F, const float* gain, const float* modl, int sh_off, int sc_off, int nrows, const float* slab_gate) {
;     ...
;     NR_LOAD(r0, 0); NR_LOAD(r1, 1); NR_LOAD(r2, 2); NR_LOAD(r3, 3); NR_LOAD(r4, 4); NR_LOAD(r5, 5); NR_LOAD(r6, 6); NR_LOAD(r7, 7);
;     { const GAS f32x4* g4 = (const GAS f32x4*)gain;
;       for (int q = F.tid; q < 5 * D / 4; q += NWAVES * 64) { const int bq = q >> 9, cq = q & 511; const GAS f32x4* mb4 = (const GAS f32x4*)(modl + (size_t)bq * MOD_LD);
;           ((LAS f32x4*)CA)[q] = g4[cq] * (mb4[sc_off / 4 + cq] + 1.0f); ((LAS f32x4*)CB)[q] = mb4[sh_off / 4 + cq]; } }
;     asm volatile("s_waitcnt lgkmcnt(0)" ::: "memory"); __builtin_amdgcn_s_barrier(); asm volatile("" ::: "memory");
;     NR_FINISH(r0, nw,            (nw) >> 12);
;     NR_FINISH(r1, nw + 2048,     (nw + 2048) >> 12);
;     NR_FINISH(r2, nw + 2 * 2048, (nw + 2 * 2048) >> 12);
	v_fma_f32 v74, v74, v112, v116
	v_fma_f32 v75, v75, v113, v117
	v_cvt_f32_f16_sdwa v117, v104 dst_sel:DWORD dst_unused:UNUSED_PAD src0_sel:WORD_1
	v_fma_f32 v4, v4, v110, v114
	v_fma_f32 v5, v5, v111, v115
	v_cvt_f32_f16_e32 v116, v104
	v_cvt_pk_bf16_f32 v4, v4, v5
	v_cvt_pk_bf16_f32 v5, v74, v75
	global_store_dwordx2 v[108:109], v[4:5], off offset:3584
	v_cvt_f32_f16_sdwa v109, v103 dst_sel:DWORD dst_unused:UNUSED_PAD src0_sel:WORD_1
	s_waitcnt vmcnt(60)
	v_cvt_f32_f16_sdwa v111, v100 dst_sel:DWORD dst_unused:UNUSED_PAD src0_sel:WORD_1
	v_mov_b32_e32 v74, v121
	v_mov_b32_e32 v75, v117
	v_cvt_f32_f16_e32 v108, v103
	v_cvt_f32_f16_e32 v110, v100
	v_cvt_f32_f16_sdwa v113, v101 dst_sel:DWORD dst_unused:UNUSED_PAD src0_sel:WORD_1
	v_mov_b32_e32 v4, v120
	v_mov_b32_e32 v5, v116
	v_mul_f32_e32 v74, v74, v74
	v_mul_f32_e32 v75, v75, v75
	v_mov_b32_e32 v104, v123
	v_mov_b32_e32 v105, v119
	v_cvt_f32_f16_e32 v112, v101
	v_fma_f32 v4, v4, v4, v74
	v_fma_f32 v5, v5, v5, v75
	v_mov_b32_e32 v74, v122
	v_mov_b32_e32 v75, v118
	v_mul_f32_e32 v104, v104, v104
	v_mul_f32_e32 v105, v105, v105
	v_mov_b32_e32 v102, v107
	v_fma_f32 v74, v74, v74, v104
	v_fma_f32 v75, v75, v75, v105
	v_mov_b32_e32 v103, v109
	v_mul_f32_e32 v100, v111, v111
	v_add_f32_e32 v4, v4, v74
	v_add_f32_e32 v5, v5, v75
	v_mov_b32_e32 v74, v106
	v_mov_b32_e32 v75, v108
	v_mul_f32_e32 v102, v102, v102
	v_mul_f32_e32 v103, v103, v103
	v_fma_f32 v104, v110, v110, v100
	v_fma_f32 v105, v111, v111, v100
	v_mul_f32_e32 v100, v113, v113
	v_fma_f32 v74, v74, v74, v102
	v_fma_f32 v75, v75, v75, v103
	v_fma_f32 v114, v112, v112, v100
	v_fma_f32 v115, v113, v113, v100
	s_waitcnt vmcnt(59)
	v_cvt_f32_f16_sdwa v101, v98 dst_sel:DWORD dst_unused:UNUSED_PAD src0_sel:WORD_1
	v_cvt_f32_f16_e32 v100, v98
	v_cvt_f32_f16_sdwa v103, v99 dst_sel:DWORD dst_unused:UNUSED_PAD src0_sel:WORD_1
	v_cvt_f32_f16_e32 v102, v99
	v_pk_add_f32 v[4:5], v[4:5], v[4:5] op_sel:[0,1] op_sel_hi:[1,0]
	v_pk_add_f32 v[74:75], v[74:75], v[74:75] op_sel:[0,1] op_sel_hi:[1,0]
	v_mul_f32_e32 v98, v100, v100
	v_mul_f32_e32 v99, v101, v101
	v_mul_f32_e32 v124, v102, v102
	v_mul_f32_e32 v125, v103, v103
	v_mov_b32_e32 v5, v98
	v_mov_b32_e32 v75, v99
	v_mov_b32_e32 v105, v124
	v_mov_b32_e32 v115, v125
	v_add_f32_e32 v4, v4, v74
	v_add_f32_e32 v5, v5, v75
	v_add_f32_e32 v74, v104, v114
	v_add_f32_e32 v75, v105, v115
	s_waitcnt vmcnt(58)
	v_cvt_f32_f16_sdwa v99, v96 dst_sel:DWORD dst_unused:UNUSED_PAD src0_sel:WORD_1
	v_cvt_f32_f16_sdwa v105, v97 dst_sel:DWORD dst_unused:UNUSED_PAD src0_sel:WORD_1
	v_cvt_f32_f16_e32 v98, v96
	v_cvt_f32_f16_e32 v104, v97
	v_add_f32_e32 v4, v4, v74
	v_add_f32_e32 v5, v5, v75
	v_mov_b32_e32 v74, v99
	v_mov_b32_e32 v75, v105
	v_add_f32_e32 v114, v4, v5
	v_add_f32_e32 v115, v5, v4
	v_mov_b32_e32 v4, v98
	v_mov_b32_e32 v5, v104
	v_mul_f32_e32 v74, v74, v74
	v_mul_f32_e32 v75, v75, v75
	s_waitcnt vmcnt(57)
	v_cvt_f32_f16_sdwa v97, v95 dst_sel:DWORD dst_unused:UNUSED_PAD src0_sel:WORD_1
	v_fma_f32 v4, v4, v4, v74
	v_fma_f32 v5, v5, v5, v75
	v_cvt_f32_f16_e32 v96, v95
	v_add_f32_e32 v124, v4, v5
	v_add_f32_e32 v125, v5, v4
	v_cvt_f32_f16_sdwa v5, v94 dst_sel:DWORD dst_unused:UNUSED_PAD src0_sel:WORD_1
	v_cvt_f32_f16_e32 v4, v94
	s_waitcnt vmcnt(56)
	v_cvt_f32_f16_sdwa v95, v93 dst_sel:DWORD dst_unused:UNUSED_PAD src0_sel:WORD_1
	v_cvt_f32_f16_e32 v94, v93
	v_mul_f32_e32 v74, v5, v5
	v_fma_f32 v126, v4, v4, v74
	v_fma_f32 v127, v5, v5, v74
	v_mul_f32_e32 v74, v97, v97
	v_fma_f32 v128, v96, v96, v74
	v_fma_f32 v129, v97, v97, v74
	v_cvt_f32_f16_sdwa v75, v92 dst_sel:DWORD dst_unused:UNUSED_PAD src0_sel:WORD_1
	v_cvt_f32_f16_e32 v74, v92
	v_mul_f32_e32 v130, v94, v94
	v_mul_f32_e32 v131, v95, v95
	v_mul_f32_e32 v92, v74, v74
	v_mul_f32_e32 v93, v75, v75
	s_nop 0
	v_mov_b32_e32 v115, v92
	v_mov_b32_e32 v125, v93
	v_mov_b32_e32 v127, v130
	v_mov_b32_e32 v129, v131
	v_add_f32_e32 v92, v114, v124
	v_add_f32_e32 v93, v115, v125
	v_add_f32_e32 v114, v126, v128
	v_add_f32_e32 v115, v127, v129
	s_nop 0
	v_add_f32_e32 v92, v92, v114
	v_add_f32_e32 v93, v93, v115
	s_nop 0
	v_add_f32_e32 v92, v92, v93
	s_nop 1
	v_add_f32_dpp v92, v92, v92 quad_perm:[1,0,3,2] row_mask:0xf bank_mask:0xf bound_ctrl:1
	s_nop 1
	v_add_f32_dpp v92, v92, v92 quad_perm:[2,3,0,1] row_mask:0xf bank_mask:0xf bound_ctrl:1
	s_nop 1
	v_add_f32_dpp v92, v92, v92 row_half_mirror row_mask:0xf bank_mask:0xf bound_ctrl:1
	s_nop 1
	v_add_f32_dpp v92, v92, v92 row_mirror row_mask:0xf bank_mask:0xf bound_ctrl:1
	s_nop 0
	v_readlane_b32 s8, v92, 16
	v_readlane_b32 s9, v92, 48
	v_readlane_b32 s6, v92, 0
	v_readlane_b32 s7, v92, 32
	v_mov_b32_e32 v92, s8
	v_mov_b32_e32 v93, s9
	v_add_f32_e32 v92, s6, v92
	v_add_f32_e32 v93, s7, v93
	s_nop 0
	v_add_f32_e32 v92, v92, v93
	v_fmamk_f32 v92, v92, 0x3a000000, v252
	v_cmp_gt_f32_e32 vcc, s55, v92
	v_mul_f32_e32 v93, 0x4f800000, v92
	s_nop 0
	v_cndmask_b32_e32 v92, v92, v93, vcc
	v_sqrt_f32_e32 v93, v92
	s_nop 0
	v_add_u32_e32 v114, -1, v93
	v_fma_f32 v115, -v114, v93, v92
	v_cmp_ge_f32_e64 s[8:9], 0, v115
	v_add_u32_e32 v115, 1, v93
	s_nop 0
	v_cndmask_b32_e64 v114, v93, v114, s[8:9]
	v_fma_f32 v93, -v115, v93, v92
	v_cmp_lt_f32_e64 s[8:9], 0, v93
	s_nop 1
	v_cndmask_b32_e64 v93, v114, v115, s[8:9]
	v_mul_f32_e32 v114, 0x37800000, v93
	v_cndmask_b32_e32 v93, v93, v114, vcc
	v_cmp_class_f32_e32 vcc, v92, v253
	s_nop 1
	v_cndmask_b32_e32 v92, v93, v92, vcc
	v_div_scale_f32 v93, s[6:7], v92, v92, 1.0
	v_rcp_f32_e32 v114, v93
	s_lshl_b32 s6, s36, 1
	s_and_b32 s6, s6, 0xffffe000
	s_add_i32 s6, s6, 0
	v_fma_f32 v115, -v93, v114, 1.0
	v_fmac_f32_e32 v114, v115, v114
	v_div_scale_f32 v115, vcc, 1.0, v92, 1.0
	v_mul_f32_e32 v124, v115, v114
	v_fma_f32 v125, -v93, v124, v115
	v_fmac_f32_e32 v124, v125, v114
	v_fma_f32 v93, -v93, v124, v115
	v_div_fmas_f32 v93, v93, v114, v124
	v_div_fixup_f32 v114, v93, v92, 1.0
	v_mul_f32_e32 v128, v120, v114
	v_mul_f32_e32 v129, v121, v114
	v_mul_f32_e32 v130, v122, v114
	v_mul_f32_e32 v131, v123, v114
	v_add_u32_e32 v115, s6, v0
	ds_read_b128 v[120:123], v115
	ds_read_b128 v[124:127], v115 offset:40960
	v_lshl_add_u64 v[92:93], s[40:41], 1, v[2:3]
	v_lshl_add_u64 v[92:93], v[92:93], 0, v[6:7]
	v_mul_f32_e32 v4, v4, v114
	v_mul_f32_e32 v5, v5, v114
	s_waitcnt lgkmcnt(0)
; #define GAS __attribute__((address_space(1)))
; #define LAS __attribute__((address_space(3)))
; #define NR_LOAD(dst, k_) do { const GAS v2u* xr_ = (const GAS v2u*)(X + (size_t)(nw + 2048 * (k_)) * D) + F.lane; \
;         _Pragma("unroll") for (int j = 0; j < 8; ++j) dst[j] = __builtin_nontemporal_load(xr_ + 64 * j); } while (0)
; __device__ __forceinline__ void norm_mod_phase2(const Args& a, Frame& F, const float* gain, const float* modl, int sh_off, int sc_off, int nrows, const float* slab_gate) {
;     ...
;     NR_LOAD(r0, 0); NR_LOAD(r1, 1); NR_LOAD(r2, 2); NR_LOAD(r3, 3); NR_LOAD(r4, 4); NR_LOAD(r5, 5); NR_LOAD(r6, 6); NR_LOAD(r7, 7);
;     { const GAS f32x4* g4 = (const GAS f32x4*)gain;
;       for (int q = F.tid; q < 5 * D / 4; q += NWAVES * 64) { const int bq = q >> 9, cq = q & 511; const GAS f32x4* mb4 = (const GAS f32x4*)(modl + (size_t)bq * MOD_LD);
;           ((LAS f32x4*)CA)[q] = g4[cq] * (mb4[sc_off / 4 + cq] + 1.0f); ((LAS f32x4*)CB)[q] = mb4[sh_off / 4 + cq]; } }
;     asm volatile("s_waitcnt lgkmcnt(0)" ::: "memory"); __builtin_amdgcn_s_barrier(); asm volatile("" ::: "memory");
;     NR_FINISH(r0, nw,            (nw) >> 12);
;     NR_FINISH(r1, nw + 2048,     (nw + 2048) >> 12);
;     NR_FINISH(r2, nw + 2 * 2048, (nw + 2 * 2048) >> 12);
;     NR_FINISH(r3, nw + 3 * 2048, (nw + 3 * 2048) >> 12);
	v_fma_f32 v122, v122, v130, v126
	v_fma_f32 v123, v123, v131, v127
	v_fma_f32 v120, v120, v128, v124
	v_fma_f32 v121, v121, v129, v125
	v_mul_f32_e32 v124, v116, v114
	v_mul_f32_e32 v125, v117, v114
	v_cvt_pk_bf16_f32 v120, v120, v121
	v_cvt_pk_bf16_f32 v121, v122, v123
	global_store_dwordx2 v[92:93], v[120:121], off
	v_mul_f32_e32 v126, v118, v114
	v_mul_f32_e32 v127, v119, v114
	ds_read_b128 v[116:119], v115 offset:1024
	ds_read_b128 v[120:123], v115 offset:41984
	s_waitcnt lgkmcnt(0)
	v_fma_f32 v118, v118, v126, v122
	v_fma_f32 v119, v119, v127, v123
	v_fma_f32 v116, v116, v124, v120
	v_fma_f32 v117, v117, v125, v121
	v_mul_f32_e32 v120, v106, v114
	v_mul_f32_e32 v121, v107, v114
	v_cvt_pk_bf16_f32 v116, v116, v117
	v_cvt_pk_bf16_f32 v117, v118, v119
	global_store_dwordx2 v[92:93], v[116:117], off offset:512
	v_mul_f32_e32 v122, v108, v114
	v_mul_f32_e32 v123, v109, v114
	ds_read_b128 v[106:109], v115 offset:2048
	ds_read_b128 v[116:119], v115 offset:43008
	s_waitcnt lgkmcnt(0)
	v_fma_f32 v108, v108, v122, v118
	v_fma_f32 v109, v109, v123, v119
	v_fma_f32 v106, v106, v120, v116
	v_fma_f32 v107, v107, v121, v117
	v_mul_f32_e32 v116, v110, v114
	v_mul_f32_e32 v117, v111, v114
	v_cvt_pk_bf16_f32 v106, v106, v107
	v_cvt_pk_bf16_f32 v107, v108, v109
	global_store_dwordx2 v[92:93], v[106:107], off offset:1024
	v_mul_f32_e32 v118, v112, v114
	v_mul_f32_e32 v119, v113, v114
	ds_read_b128 v[106:109], v115 offset:3072
	ds_read_b128 v[110:113], v115 offset:44032
	s_waitcnt lgkmcnt(0)
	v_fma_f32 v108, v118, v108, v112
	v_fma_f32 v109, v119, v109, v113
	v_fma_f32 v106, v116, v106, v110
	v_fma_f32 v107, v117, v107, v111
	v_mul_f32_e32 v110, v100, v114
	v_mul_f32_e32 v111, v101, v114
	v_cvt_pk_bf16_f32 v106, v106, v107
	v_cvt_pk_bf16_f32 v107, v108, v109
	global_store_dwordx2 v[92:93], v[106:107], off offset:1536
	v_mul_f32_e32 v112, v102, v114
	v_mul_f32_e32 v113, v103, v114
	ds_read_b128 v[100:103], v115 offset:4096
	ds_read_b128 v[106:109], v115 offset:45056
	s_waitcnt lgkmcnt(0)
	v_fma_f32 v102, v112, v102, v108
	v_fma_f32 v103, v113, v103, v109
	v_fma_f32 v100, v110, v100, v106
	v_fma_f32 v101, v111, v101, v107
	v_mul_f32_e32 v106, v98, v114
	v_mul_f32_e32 v107, v99, v114
	v_cvt_pk_bf16_f32 v100, v100, v101
	v_cvt_pk_bf16_f32 v101, v102, v103
	global_store_dwordx2 v[92:93], v[100:101], off offset:2048
	v_mul_f32_e32 v108, v104, v114
	v_mul_f32_e32 v109, v105, v114
	ds_read_b128 v[98:101], v115 offset:5120
	ds_read_b128 v[102:105], v115 offset:46080
	s_waitcnt lgkmcnt(0)
	v_fma_f32 v100, v108, v100, v104
	v_fma_f32 v101, v109, v101, v105
	v_fma_f32 v98, v106, v98, v102
	v_fma_f32 v99, v107, v99, v103
	v_mul_f32_e32 v104, v96, v114
	v_mul_f32_e32 v105, v97, v114
	v_cvt_pk_bf16_f32 v98, v98, v99
	v_cvt_pk_bf16_f32 v99, v100, v101
	global_store_dwordx2 v[92:93], v[98:99], off offset:2560
	ds_read_b128 v[96:99], v115 offset:6144
	ds_read_b128 v[100:103], v115 offset:47104
	s_waitcnt vmcnt(61)
	v_cvt_f32_f16_sdwa v107, v91 dst_sel:DWORD dst_unused:UNUSED_PAD src0_sel:WORD_1
	v_cvt_f32_f16_e32 v106, v91
	s_waitcnt vmcnt(59)
	v_cvt_f32_f16_sdwa v91, v86 dst_sel:DWORD dst_unused:UNUSED_PAD src0_sel:WORD_1
	s_waitcnt lgkmcnt(0)
	v_fma_f32 v98, v104, v98, v102
	v_fma_f32 v99, v105, v99, v103
	v_fma_f32 v4, v4, v96, v100
	v_fma_f32 v5, v5, v97, v101
	v_cvt_f32_f16_sdwa v105, v90 dst_sel:DWORD dst_unused:UNUSED_PAD src0_sel:WORD_1
	v_cvt_pk_bf16_f32 v4, v4, v5
	v_cvt_pk_bf16_f32 v5, v98, v99
	global_store_dwordx2 v[92:93], v[4:5], off offset:3072
	v_mul_f32_e32 v4, v74, v114
	v_mul_f32_e32 v5, v75, v114
	v_mul_f32_e32 v74, v94, v114
	v_mul_f32_e32 v75, v95, v114
	ds_read_b128 v[94:97], v115 offset:7168
	ds_read_b128 v[98:101], v115 offset:48128
	v_cvt_f32_f16_e32 v104, v90
	v_cvt_f32_f16_sdwa v103, v89 dst_sel:DWORD dst_unused:UNUSED_PAD src0_sel:WORD_1
	v_cvt_f32_f16_e32 v102, v89
	v_cvt_f32_f16_e32 v90, v86
	s_waitcnt lgkmcnt(0)
	v_fma_f32 v74, v74, v96, v100
	v_fma_f32 v75, v75, v97, v101
	v_cvt_f32_f16_sdwa v101, v88 dst_sel:DWORD dst_unused:UNUSED_PAD src0_sel:WORD_1
	v_fma_f32 v4, v4, v94, v98
	v_fma_f32 v5, v5, v95, v99
	v_cvt_f32_f16_e32 v100, v88
	v_cvt_pk_bf16_f32 v4, v4, v5
	v_cvt_pk_bf16_f32 v5, v74, v75
	global_store_dwordx2 v[92:93], v[4:5], off offset:3584
	v_cvt_f32_f16_sdwa v93, v87 dst_sel:DWORD dst_unused:UNUSED_PAD src0_sel:WORD_1
	s_waitcnt vmcnt(60)
	v_cvt_f32_f16_sdwa v95, v84 dst_sel:DWORD dst_unused:UNUSED_PAD src0_sel:WORD_1
	v_mov_b32_e32 v74, v105
	v_mov_b32_e32 v75, v101
	v_cvt_f32_f16_e32 v92, v87
	v_cvt_f32_f16_e32 v94, v84
	v_cvt_f32_f16_sdwa v97, v85 dst_sel:DWORD dst_unused:UNUSED_PAD src0_sel:WORD_1
	v_mov_b32_e32 v4, v104
	v_mov_b32_e32 v5, v100
	v_mul_f32_e32 v74, v74, v74
	v_mul_f32_e32 v75, v75, v75
	v_mov_b32_e32 v88, v107
	v_mov_b32_e32 v89, v103
	v_cvt_f32_f16_e32 v96, v85
	v_fma_f32 v4, v4, v4, v74
	v_fma_f32 v5, v5, v5, v75
	v_mov_b32_e32 v74, v106
	v_mov_b32_e32 v75, v102
	v_mul_f32_e32 v88, v88, v88
	v_mul_f32_e32 v89, v89, v89
	v_mov_b32_e32 v86, v91
	v_fma_f32 v74, v74, v74, v88
	v_fma_f32 v75, v75, v75, v89
	v_mov_b32_e32 v87, v93
	v_mul_f32_e32 v84, v95, v95
	v_add_f32_e32 v4, v4, v74
	v_add_f32_e32 v5, v5, v75
	v_mov_b32_e32 v74, v90
	v_mov_b32_e32 v75, v92
	v_mul_f32_e32 v86, v86, v86
	v_mul_f32_e32 v87, v87, v87
	v_fma_f32 v88, v94, v94, v84
	v_fma_f32 v89, v95, v95, v84
	v_mul_f32_e32 v84, v97, v97
	v_fma_f32 v74, v74, v74, v86
	v_fma_f32 v75, v75, v75, v87
	v_fma_f32 v98, v96, v96, v84
	v_fma_f32 v99, v97, v97, v84
	s_waitcnt vmcnt(59)
; #define GAS __attribute__((address_space(1)))
; #define LAS __attribute__((address_space(3)))
; #define NR_LOAD(dst, k_) do { const GAS v2u* xr_ = (const GAS v2u*)(X + (size_t)(nw + 2048 * (k_)) * D) + F.lane; \
;         _Pragma("unroll") for (int j = 0; j < 8; ++j) dst[j] = __builtin_nontemporal_load(xr_ + 64 * j); } while (0)
; __device__ __forceinline__ void norm_mod_phase2(const Args& a, Frame& F, const float* gain, const float* modl, int sh_off, int sc_off, int nrows, const float* slab_gate) {
;     ...
;     NR_LOAD(r0, 0); NR_LOAD(r1, 1); NR_LOAD(r2, 2); NR_LOAD(r3, 3); NR_LOAD(r4, 4); NR_LOAD(r5, 5); NR_LOAD(r6, 6); NR_LOAD(r7, 7);
;     { const GAS f32x4* g4 = (const GAS f32x4*)gain;
;       for (int q = F.tid; q < 5 * D / 4; q += NWAVES * 64) { const int bq = q >> 9, cq = q & 511; const GAS f32x4* mb4 = (const GAS f32x4*)(modl + (size_t)bq * MOD_LD);
;           ((LAS f32x4*)CA)[q] = g4[cq] * (mb4[sc_off / 4 + cq] + 1.0f); ((LAS f32x4*)CB)[q] = mb4[sh_off / 4 + cq]; } }
;     asm volatile("s_waitcnt lgkmcnt(0)" ::: "memory"); __builtin_amdgcn_s_barrier(); asm volatile("" ::: "memory");
;     NR_FINISH(r0, nw,            (nw) >> 12);
;     NR_FINISH(r1, nw + 2048,     (nw + 2048) >> 12);
;     NR_FINISH(r2, nw + 2 * 2048, (nw + 2 * 2048) >> 12);
;     NR_FINISH(r3, nw + 3 * 2048, (nw + 3 * 2048) >> 12);
	v_cvt_f32_f16_sdwa v85, v82 dst_sel:DWORD dst_unused:UNUSED_PAD src0_sel:WORD_1
	v_cvt_f32_f16_e32 v84, v82
	v_cvt_f32_f16_sdwa v87, v83 dst_sel:DWORD dst_unused:UNUSED_PAD src0_sel:WORD_1
	v_cvt_f32_f16_e32 v86, v83
	v_pk_add_f32 v[4:5], v[4:5], v[4:5] op_sel:[0,1] op_sel_hi:[1,0]
	v_pk_add_f32 v[74:75], v[74:75], v[74:75] op_sel:[0,1] op_sel_hi:[1,0]
	v_mul_f32_e32 v82, v84, v84
	v_mul_f32_e32 v83, v85, v85
	v_mul_f32_e32 v108, v86, v86
	v_mul_f32_e32 v109, v87, v87
	v_mov_b32_e32 v5, v82
	v_mov_b32_e32 v75, v83
	v_mov_b32_e32 v89, v108
	v_mov_b32_e32 v99, v109
	v_add_f32_e32 v4, v4, v74
	v_add_f32_e32 v5, v5, v75
	v_add_f32_e32 v74, v88, v98
	v_add_f32_e32 v75, v89, v99
	s_waitcnt vmcnt(58)
	v_cvt_f32_f16_sdwa v83, v80 dst_sel:DWORD dst_unused:UNUSED_PAD src0_sel:WORD_1
	v_cvt_f32_f16_sdwa v89, v81 dst_sel:DWORD dst_unused:UNUSED_PAD src0_sel:WORD_1
	v_cvt_f32_f16_e32 v82, v80
	v_cvt_f32_f16_e32 v88, v81
	v_add_f32_e32 v4, v4, v74
	v_add_f32_e32 v5, v5, v75
	v_mov_b32_e32 v74, v83
	v_mov_b32_e32 v75, v89
	v_add_f32_e32 v98, v4, v5
	v_add_f32_e32 v99, v5, v4
	v_mov_b32_e32 v4, v82
	v_mov_b32_e32 v5, v88
	v_mul_f32_e32 v74, v74, v74
	v_mul_f32_e32 v75, v75, v75
	s_waitcnt vmcnt(57)
	v_cvt_f32_f16_sdwa v81, v79 dst_sel:DWORD dst_unused:UNUSED_PAD src0_sel:WORD_1
	v_fma_f32 v4, v4, v4, v74
	v_fma_f32 v5, v5, v5, v75
	v_cvt_f32_f16_e32 v80, v79
	v_add_f32_e32 v108, v4, v5
	v_add_f32_e32 v109, v5, v4
	v_cvt_f32_f16_sdwa v5, v78 dst_sel:DWORD dst_unused:UNUSED_PAD src0_sel:WORD_1
	v_cvt_f32_f16_e32 v4, v78
	s_waitcnt vmcnt(56)
	v_cvt_f32_f16_sdwa v79, v77 dst_sel:DWORD dst_unused:UNUSED_PAD src0_sel:WORD_1
	v_cvt_f32_f16_e32 v78, v77
	v_mul_f32_e32 v74, v5, v5
	v_fma_f32 v110, v4, v4, v74
	v_fma_f32 v111, v5, v5, v74
	v_mul_f32_e32 v74, v81, v81
	v_fma_f32 v112, v80, v80, v74
	v_fma_f32 v113, v81, v81, v74
	v_cvt_f32_f16_sdwa v75, v76 dst_sel:DWORD dst_unused:UNUSED_PAD src0_sel:WORD_1
	v_cvt_f32_f16_e32 v74, v76
	v_mul_f32_e32 v114, v78, v78
	v_mul_f32_e32 v115, v79, v79
	v_mul_f32_e32 v76, v74, v74
	v_mul_f32_e32 v77, v75, v75
	s_nop 0
	v_mov_b32_e32 v99, v76
	v_mov_b32_e32 v109, v77
	v_mov_b32_e32 v111, v114
	v_mov_b32_e32 v113, v115
	v_add_f32_e32 v76, v98, v108
	v_add_f32_e32 v77, v99, v109
	v_add_f32_e32 v98, v110, v112
	v_add_f32_e32 v99, v111, v113
	s_nop 0
	v_add_f32_e32 v76, v76, v98
	v_add_f32_e32 v77, v77, v99
	s_nop 0
	v_add_f32_e32 v76, v76, v77
	s_nop 1
	v_add_f32_dpp v76, v76, v76 quad_perm:[1,0,3,2] row_mask:0xf bank_mask:0xf bound_ctrl:1
	s_nop 1
	v_add_f32_dpp v76, v76, v76 quad_perm:[2,3,0,1] row_mask:0xf bank_mask:0xf bound_ctrl:1
	s_nop 1
	v_add_f32_dpp v76, v76, v76 row_half_mirror row_mask:0xf bank_mask:0xf bound_ctrl:1
	s_nop 1
	v_add_f32_dpp v76, v76, v76 row_mirror row_mask:0xf bank_mask:0xf bound_ctrl:1
	s_nop 0
	v_readlane_b32 s8, v76, 16
	v_readlane_b32 s9, v76, 48
	v_readlane_b32 s6, v76, 0
	v_readlane_b32 s7, v76, 32
	v_mov_b32_e32 v76, s8
	v_mov_b32_e32 v77, s9
	v_add_f32_e32 v76, s6, v76
	v_add_f32_e32 v77, s7, v77
	s_nop 0
	v_add_f32_e32 v76, v76, v77
	v_fmamk_f32 v76, v76, 0x3a000000, v252
	v_cmp_gt_f32_e32 vcc, s55, v76
	v_mul_f32_e32 v77, 0x4f800000, v76
	s_nop 0
	v_cndmask_b32_e32 v76, v76, v77, vcc
	v_sqrt_f32_e32 v77, v76
	s_nop 0
	v_add_u32_e32 v98, -1, v77
	v_fma_f32 v99, -v98, v77, v76
	v_cmp_ge_f32_e64 s[8:9], 0, v99
	v_add_u32_e32 v99, 1, v77
	s_nop 0
	v_cndmask_b32_e64 v98, v77, v98, s[8:9]
	v_fma_f32 v77, -v99, v77, v76
	v_cmp_lt_f32_e64 s[8:9], 0, v77
	s_nop 1
	v_cndmask_b32_e64 v77, v98, v99, s[8:9]
	v_mul_f32_e32 v98, 0x37800000, v77
	v_cndmask_b32_e32 v77, v77, v98, vcc
	v_cmp_class_f32_e32 vcc, v76, v253
	s_nop 1
	v_cndmask_b32_e32 v76, v77, v76, vcc
	v_div_scale_f32 v77, s[6:7], v76, v76, 1.0
	v_rcp_f32_e32 v98, v77
	s_lshl_b32 s6, s30, 1
	s_and_b32 s6, s6, 0xffffe000
	s_add_i32 s6, s6, 0
	v_fma_f32 v99, -v77, v98, 1.0
	v_fmac_f32_e32 v98, v99, v98
	v_div_scale_f32 v99, vcc, 1.0, v76, 1.0
	v_mul_f32_e32 v108, v99, v98
	v_fma_f32 v109, -v77, v108, v99
	v_fmac_f32_e32 v108, v109, v98
	v_fma_f32 v77, -v77, v108, v99
	v_div_fmas_f32 v77, v77, v98, v108
	v_div_fixup_f32 v98, v77, v76, 1.0
	v_mul_f32_e32 v112, v104, v98
	v_mul_f32_e32 v113, v105, v98
	v_mul_f32_e32 v114, v106, v98
	v_mul_f32_e32 v115, v107, v98
	v_add_u32_e32 v99, s6, v0
	ds_read_b128 v[104:107], v99
	ds_read_b128 v[108:111], v99 offset:40960
	v_lshl_add_u64 v[76:77], s[34:35], 1, v[2:3]
	v_lshl_add_u64 v[76:77], v[76:77], 0, v[6:7]
	v_mul_f32_e32 v4, v4, v98
	v_mul_f32_e32 v5, v5, v98
	s_waitcnt lgkmcnt(0)
	v_fma_f32 v106, v106, v114, v110
	v_fma_f32 v107, v107, v115, v111
	v_fma_f32 v104, v104, v112, v108
	v_fma_f32 v105, v105, v113, v109
	v_mul_f32_e32 v108, v100, v98
	v_mul_f32_e32 v109, v101, v98
	v_cvt_pk_bf16_f32 v104, v104, v105
	v_cvt_pk_bf16_f32 v105, v106, v107
	global_store_dwordx2 v[76:77], v[104:105], off
	v_mul_f32_e32 v110, v102, v98
	v_mul_f32_e32 v111, v103, v98
	ds_read_b128 v[100:103], v99 offset:1024
	ds_read_b128 v[104:107], v99 offset:41984
	s_waitcnt lgkmcnt(0)
	v_fma_f32 v102, v102, v110, v106
	v_fma_f32 v103, v103, v111, v107
	v_fma_f32 v100, v100, v108, v104
	v_fma_f32 v101, v101, v109, v105
	v_mul_f32_e32 v104, v90, v98
	v_mul_f32_e32 v105, v91, v98
	v_cvt_pk_bf16_f32 v100, v100, v101
	v_cvt_pk_bf16_f32 v101, v102, v103
	global_store_dwordx2 v[76:77], v[100:101], off offset:512
	v_mul_f32_e32 v106, v92, v98
	v_mul_f32_e32 v107, v93, v98
	ds_read_b128 v[90:93], v99 offset:2048
	ds_read_b128 v[100:103], v99 offset:43008
	s_waitcnt lgkmcnt(0)
; #define GAS __attribute__((address_space(1)))
; #define LAS __attribute__((address_space(3)))
; #define NR_LOAD(dst, k_) do { const GAS v2u* xr_ = (const GAS v2u*)(X + (size_t)(nw + 2048 * (k_)) * D) + F.lane; \
;         _Pragma("unroll") for (int j = 0; j < 8; ++j) dst[j] = __builtin_nontemporal_load(xr_ + 64 * j); } while (0)
; __device__ __forceinline__ void norm_mod_phase2(const Args& a, Frame& F, const float* gain, const float* modl, int sh_off, int sc_off, int nrows, const float* slab_gate) {
;     ...
;     NR_LOAD(r0, 0); NR_LOAD(r1, 1); NR_LOAD(r2, 2); NR_LOAD(r3, 3); NR_LOAD(r4, 4); NR_LOAD(r5, 5); NR_LOAD(r6, 6); NR_LOAD(r7, 7);
;     { const GAS f32x4* g4 = (const GAS f32x4*)gain;
;       for (int q = F.tid; q < 5 * D / 4; q += NWAVES * 64) { const int bq = q >> 9, cq = q & 511; const GAS f32x4* mb4 = (const GAS f32x4*)(modl + (size_t)bq * MOD_LD);
;           ((LAS f32x4*)CA)[q] = g4[cq] * (mb4[sc_off / 4 + cq] + 1.0f); ((LAS f32x4*)CB)[q] = mb4[sh_off / 4 + cq]; } }
;     asm volatile("s_waitcnt lgkmcnt(0)" ::: "memory"); __builtin_amdgcn_s_barrier(); asm volatile("" ::: "memory");
;     NR_FINISH(r0, nw,            (nw) >> 12);
;     NR_FINISH(r1, nw + 2048,     (nw + 2048) >> 12);
;     NR_FINISH(r2, nw + 2 * 2048, (nw + 2 * 2048) >> 12);
;     NR_FINISH(r3, nw + 3 * 2048, (nw + 3 * 2048) >> 12);
;     NR_FINISH(r4, nw + 4 * 2048, (nw + 4 * 2048) >> 12);
	v_fma_f32 v92, v92, v106, v102
	v_fma_f32 v93, v93, v107, v103
	v_fma_f32 v90, v90, v104, v100
	v_fma_f32 v91, v91, v105, v101
	v_mul_f32_e32 v100, v94, v98
	v_mul_f32_e32 v101, v95, v98
	v_cvt_pk_bf16_f32 v90, v90, v91
	v_cvt_pk_bf16_f32 v91, v92, v93
	global_store_dwordx2 v[76:77], v[90:91], off offset:1024
	v_mul_f32_e32 v102, v96, v98
	v_mul_f32_e32 v103, v97, v98
	ds_read_b128 v[90:93], v99 offset:3072
	ds_read_b128 v[94:97], v99 offset:44032
	s_waitcnt lgkmcnt(0)
	v_fma_f32 v92, v102, v92, v96
	v_fma_f32 v93, v103, v93, v97
	v_fma_f32 v90, v100, v90, v94
	v_fma_f32 v91, v101, v91, v95
	v_mul_f32_e32 v94, v84, v98
	v_mul_f32_e32 v95, v85, v98
	v_cvt_pk_bf16_f32 v90, v90, v91
	v_cvt_pk_bf16_f32 v91, v92, v93
	global_store_dwordx2 v[76:77], v[90:91], off offset:1536
	v_mul_f32_e32 v96, v86, v98
	v_mul_f32_e32 v97, v87, v98
	ds_read_b128 v[84:87], v99 offset:4096
	ds_read_b128 v[90:93], v99 offset:45056
	s_waitcnt lgkmcnt(0)
	v_fma_f32 v86, v96, v86, v92
	v_fma_f32 v87, v97, v87, v93
	v_fma_f32 v84, v94, v84, v90
	v_fma_f32 v85, v95, v85, v91
	v_mul_f32_e32 v90, v82, v98
	v_mul_f32_e32 v91, v83, v98
	v_cvt_pk_bf16_f32 v84, v84, v85
	v_cvt_pk_bf16_f32 v85, v86, v87
	global_store_dwordx2 v[76:77], v[84:85], off offset:2048
	v_mul_f32_e32 v92, v88, v98
	v_mul_f32_e32 v93, v89, v98
	ds_read_b128 v[82:85], v99 offset:5120
	ds_read_b128 v[86:89], v99 offset:46080
	s_waitcnt lgkmcnt(0)
	v_fma_f32 v84, v92, v84, v88
	v_fma_f32 v85, v93, v85, v89
	v_fma_f32 v82, v90, v82, v86
	v_fma_f32 v83, v91, v83, v87
	v_mul_f32_e32 v88, v80, v98
	v_mul_f32_e32 v89, v81, v98
	v_cvt_pk_bf16_f32 v82, v82, v83
	v_cvt_pk_bf16_f32 v83, v84, v85
	global_store_dwordx2 v[76:77], v[82:83], off offset:2560
	ds_read_b128 v[80:83], v99 offset:6144
	ds_read_b128 v[84:87], v99 offset:47104
	s_waitcnt vmcnt(61)
	v_cvt_f32_f16_sdwa v91, v73 dst_sel:DWORD dst_unused:UNUSED_PAD src0_sel:WORD_1
	v_cvt_f32_f16_e32 v90, v73
	s_waitcnt lgkmcnt(0)
	v_fma_f32 v82, v88, v82, v86
	v_fma_f32 v83, v89, v83, v87
	v_fma_f32 v4, v4, v80, v84
	v_fma_f32 v5, v5, v81, v85
	v_cvt_f32_f16_sdwa v89, v72 dst_sel:DWORD dst_unused:UNUSED_PAD src0_sel:WORD_1
	v_cvt_pk_bf16_f32 v4, v4, v5
	v_cvt_pk_bf16_f32 v5, v82, v83
	global_store_dwordx2 v[76:77], v[4:5], off offset:3072
	v_mul_f32_e32 v4, v74, v98
	v_mul_f32_e32 v5, v75, v98
	v_mul_f32_e32 v74, v78, v98
	v_mul_f32_e32 v75, v79, v98
	ds_read_b128 v[78:81], v99 offset:7168
	ds_read_b128 v[82:85], v99 offset:48128
	v_cvt_f32_f16_e32 v88, v72
	s_waitcnt vmcnt(61)
	v_cvt_f32_f16_sdwa v87, v71 dst_sel:DWORD dst_unused:UNUSED_PAD src0_sel:WORD_1
	v_cvt_f32_f16_e32 v86, v71
	v_mov_b32_e32 v72, v91
	s_waitcnt lgkmcnt(0)
	v_fma_f32 v74, v74, v80, v84
	v_fma_f32 v75, v75, v81, v85
	v_cvt_f32_f16_sdwa v85, v70 dst_sel:DWORD dst_unused:UNUSED_PAD src0_sel:WORD_1
	v_cvt_f32_f16_e32 v84, v70
	v_fma_f32 v4, v4, v78, v82
	v_fma_f32 v5, v5, v79, v83
	v_mov_b32_e32 v70, v89
	v_cvt_pk_bf16_f32 v4, v4, v5
	v_cvt_pk_bf16_f32 v5, v74, v75
	global_store_dwordx2 v[76:77], v[4:5], off offset:3584
	v_mov_b32_e32 v71, v85
	s_waitcnt vmcnt(61)
	v_cvt_f32_f16_sdwa v75, v68 dst_sel:DWORD dst_unused:UNUSED_PAD src0_sel:WORD_1
	v_cvt_f32_f16_sdwa v77, v69 dst_sel:DWORD dst_unused:UNUSED_PAD src0_sel:WORD_1
	v_mov_b32_e32 v4, v88
	v_mov_b32_e32 v5, v84
	v_mul_f32_e32 v70, v70, v70
	v_mul_f32_e32 v71, v71, v71
	v_mov_b32_e32 v73, v87
	v_cvt_f32_f16_e32 v74, v68
	v_cvt_f32_f16_e32 v76, v69
	s_waitcnt vmcnt(60)
	v_cvt_f32_f16_sdwa v79, v66 dst_sel:DWORD dst_unused:UNUSED_PAD src0_sel:WORD_1
	v_fma_f32 v4, v4, v4, v70
	v_fma_f32 v5, v5, v5, v71
	v_mov_b32_e32 v70, v90
	v_mov_b32_e32 v71, v86
	v_mul_f32_e32 v72, v72, v72
	v_mul_f32_e32 v73, v73, v73
	v_cvt_f32_f16_e32 v78, v66
	v_cvt_f32_f16_sdwa v81, v67 dst_sel:DWORD dst_unused:UNUSED_PAD src0_sel:WORD_1
	v_fma_f32 v70, v70, v70, v72
	v_fma_f32 v71, v71, v71, v73
	v_cvt_f32_f16_e32 v80, v67
	v_add_f32_e32 v4, v4, v70
	v_add_f32_e32 v5, v5, v71
	v_mov_b32_e32 v70, v75
	v_mov_b32_e32 v71, v77
	v_mov_b32_e32 v68, v74
	v_mov_b32_e32 v69, v76
	v_mul_f32_e32 v70, v70, v70
	v_mul_f32_e32 v71, v71, v71
	v_mul_f32_e32 v66, v79, v79
	v_fma_f32 v68, v68, v68, v70
	v_fma_f32 v69, v69, v69, v71
	v_fma_f32 v72, v78, v78, v66
	v_fma_f32 v73, v79, v79, v66
	v_mul_f32_e32 v66, v81, v81
	v_add_f32_e32 v70, v68, v69
	v_add_f32_e32 v71, v69, v68
	v_fma_f32 v82, v80, v80, v66
	v_fma_f32 v83, v81, v81, v66
	s_waitcnt vmcnt(59)
	v_cvt_f32_f16_sdwa v67, v64 dst_sel:DWORD dst_unused:UNUSED_PAD src0_sel:WORD_1
	v_cvt_f32_f16_e32 v66, v64
	v_cvt_f32_f16_sdwa v69, v65 dst_sel:DWORD dst_unused:UNUSED_PAD src0_sel:WORD_1
	v_cvt_f32_f16_e32 v68, v65
	v_pk_add_f32 v[4:5], v[4:5], v[4:5] op_sel:[0,1] op_sel_hi:[1,0]
	v_mul_f32_e32 v64, v66, v66
	v_mul_f32_e32 v65, v67, v67
	v_mul_f32_e32 v92, v68, v68
	v_mul_f32_e32 v93, v69, v69
	v_mov_b32_e32 v5, v64
	v_mov_b32_e32 v71, v65
	v_mov_b32_e32 v73, v92
	v_mov_b32_e32 v83, v93
	v_add_f32_e32 v4, v4, v70
	v_add_f32_e32 v5, v5, v71
	v_add_f32_e32 v64, v72, v82
	v_add_f32_e32 v65, v73, v83
	s_waitcnt vmcnt(58)
	v_cvt_f32_f16_sdwa v71, v62 dst_sel:DWORD dst_unused:UNUSED_PAD src0_sel:WORD_1
	v_cvt_f32_f16_sdwa v73, v63 dst_sel:DWORD dst_unused:UNUSED_PAD src0_sel:WORD_1
	v_cvt_f32_f16_e32 v70, v62
	v_cvt_f32_f16_e32 v72, v63
	v_add_f32_e32 v4, v4, v64
	v_add_f32_e32 v5, v5, v65
	v_mov_b32_e32 v62, v71
	v_mov_b32_e32 v63, v73
	v_add_f32_e32 v82, v4, v5
	v_add_f32_e32 v83, v5, v4
	v_mov_b32_e32 v4, v70
	v_mov_b32_e32 v5, v72
	v_mul_f32_e32 v62, v62, v62
	v_mul_f32_e32 v63, v63, v63
	s_waitcnt vmcnt(56)
; #define GAS __attribute__((address_space(1)))
; #define LAS __attribute__((address_space(3)))
; #define NR_LOAD(dst, k_) do { const GAS v2u* xr_ = (const GAS v2u*)(X + (size_t)(nw + 2048 * (k_)) * D) + F.lane; \
;         _Pragma("unroll") for (int j = 0; j < 8; ++j) dst[j] = __builtin_nontemporal_load(xr_ + 64 * j); } while (0)
; __device__ __forceinline__ void norm_mod_phase2(const Args& a, Frame& F, const float* gain, const float* modl, int sh_off, int sc_off, int nrows, const float* slab_gate) {
;     ...
;     NR_LOAD(r0, 0); NR_LOAD(r1, 1); NR_LOAD(r2, 2); NR_LOAD(r3, 3); NR_LOAD(r4, 4); NR_LOAD(r5, 5); NR_LOAD(r6, 6); NR_LOAD(r7, 7);
;     { const GAS f32x4* g4 = (const GAS f32x4*)gain;
;       for (int q = F.tid; q < 5 * D / 4; q += NWAVES * 64) { const int bq = q >> 9, cq = q & 511; const GAS f32x4* mb4 = (const GAS f32x4*)(modl + (size_t)bq * MOD_LD);
;           ((LAS f32x4*)CA)[q] = g4[cq] * (mb4[sc_off / 4 + cq] + 1.0f); ((LAS f32x4*)CB)[q] = mb4[sh_off / 4 + cq]; } }
;     asm volatile("s_waitcnt lgkmcnt(0)" ::: "memory"); __builtin_amdgcn_s_barrier(); asm volatile("" ::: "memory");
;     NR_FINISH(r0, nw,            (nw) >> 12);
;     NR_FINISH(r1, nw + 2048,     (nw + 2048) >> 12);
;     NR_FINISH(r2, nw + 2 * 2048, (nw + 2 * 2048) >> 12);
;     NR_FINISH(r3, nw + 3 * 2048, (nw + 3 * 2048) >> 12);
;     NR_FINISH(r4, nw + 4 * 2048, (nw + 4 * 2048) >> 12);
	v_cvt_f32_f16_sdwa v65, v59 dst_sel:DWORD dst_unused:UNUSED_PAD src0_sel:WORD_1
	v_fma_f32 v4, v4, v4, v62
	v_fma_f32 v5, v5, v5, v63
	v_cvt_f32_f16_sdwa v63, v61 dst_sel:DWORD dst_unused:UNUSED_PAD src0_sel:WORD_1
	v_add_f32_e32 v92, v4, v5
	v_add_f32_e32 v93, v5, v4
	v_cvt_f32_f16_sdwa v5, v60 dst_sel:DWORD dst_unused:UNUSED_PAD src0_sel:WORD_1
	v_cvt_f32_f16_e32 v4, v60
	v_cvt_f32_f16_e32 v62, v61
	v_cvt_f32_f16_e32 v64, v59
	v_mul_f32_e32 v60, v5, v5
	v_fma_f32 v94, v4, v4, v60
	v_fma_f32 v95, v5, v5, v60
	v_mul_f32_e32 v60, v63, v63
	v_fma_f32 v96, v62, v62, v60
	v_fma_f32 v97, v63, v63, v60
	v_cvt_f32_f16_sdwa v61, v58 dst_sel:DWORD dst_unused:UNUSED_PAD src0_sel:WORD_1
	v_cvt_f32_f16_e32 v60, v58
	v_mul_f32_e32 v98, v64, v64
	v_mul_f32_e32 v99, v65, v65
	v_mul_f32_e32 v58, v60, v60
	v_mul_f32_e32 v59, v61, v61
	s_nop 0
	v_mov_b32_e32 v83, v58
	v_mov_b32_e32 v93, v59
	v_mov_b32_e32 v95, v98
	v_mov_b32_e32 v97, v99
	v_add_f32_e32 v58, v82, v92
	v_add_f32_e32 v59, v83, v93
	v_add_f32_e32 v82, v94, v96
	v_add_f32_e32 v83, v95, v97
	s_nop 0
	v_add_f32_e32 v58, v58, v82
	v_add_f32_e32 v59, v59, v83
	s_nop 0
	v_add_f32_e32 v58, v58, v59
	s_nop 1
	v_add_f32_dpp v58, v58, v58 quad_perm:[1,0,3,2] row_mask:0xf bank_mask:0xf bound_ctrl:1
	s_nop 1
	v_add_f32_dpp v58, v58, v58 quad_perm:[2,3,0,1] row_mask:0xf bank_mask:0xf bound_ctrl:1
	s_nop 1
	v_add_f32_dpp v58, v58, v58 row_half_mirror row_mask:0xf bank_mask:0xf bound_ctrl:1
	s_nop 1
	v_add_f32_dpp v58, v58, v58 row_mirror row_mask:0xf bank_mask:0xf bound_ctrl:1
	s_nop 0
	v_readlane_b32 s8, v58, 16
	v_readlane_b32 s9, v58, 48
	v_readlane_b32 s6, v58, 0
	v_readlane_b32 s7, v58, 32
	v_mov_b32_e32 v58, s8
	v_mov_b32_e32 v59, s9
	v_add_f32_e32 v58, s6, v58
	v_add_f32_e32 v59, s7, v59
	s_nop 0
	v_add_f32_e32 v58, v58, v59
	v_fmamk_f32 v58, v58, 0x3a000000, v252
	v_cmp_gt_f32_e32 vcc, s55, v58
	v_mul_f32_e32 v59, 0x4f800000, v58
	s_nop 0
	v_cndmask_b32_e32 v58, v58, v59, vcc
	v_sqrt_f32_e32 v59, v58
	s_nop 0
	v_add_u32_e32 v82, -1, v59
	v_fma_f32 v83, -v82, v59, v58
	v_cmp_ge_f32_e64 s[8:9], 0, v83
	v_add_u32_e32 v83, 1, v59
	s_nop 0
	v_cndmask_b32_e64 v82, v59, v82, s[8:9]
	v_fma_f32 v59, -v83, v59, v58
	v_cmp_lt_f32_e64 s[8:9], 0, v59
	s_nop 1
	v_cndmask_b32_e64 v59, v82, v83, s[8:9]
	v_mul_f32_e32 v82, 0x37800000, v59
	v_cndmask_b32_e32 v59, v59, v82, vcc
	v_cmp_class_f32_e32 vcc, v58, v253
	s_nop 1
	v_cndmask_b32_e32 v58, v59, v58, vcc
	v_div_scale_f32 v59, s[6:7], v58, v58, 1.0
	v_rcp_f32_e32 v82, v59
	s_lshl_b32 s6, s26, 1
	s_and_b32 s6, s6, 0xffffe000
	s_add_i32 s6, s6, 0
	v_fma_f32 v83, -v59, v82, 1.0
	v_fmac_f32_e32 v82, v83, v82
	v_div_scale_f32 v83, vcc, 1.0, v58, 1.0
	v_mul_f32_e32 v92, v83, v82
	v_fma_f32 v93, -v59, v92, v83
	v_fmac_f32_e32 v92, v93, v82
	v_fma_f32 v59, -v59, v92, v83
	v_div_fmas_f32 v59, v59, v82, v92
	v_div_fixup_f32 v82, v59, v58, 1.0
	v_mul_f32_e32 v96, v88, v82
	v_mul_f32_e32 v97, v89, v82
	v_mul_f32_e32 v98, v90, v82
	v_mul_f32_e32 v99, v91, v82
	v_add_u32_e32 v83, s6, v0
	ds_read_b128 v[88:91], v83
	ds_read_b128 v[92:95], v83 offset:40960
	v_lshl_add_u64 v[58:59], s[28:29], 1, v[2:3]
	v_lshl_add_u64 v[58:59], v[58:59], 0, v[6:7]
	v_mul_f32_e32 v4, v4, v82
	v_mul_f32_e32 v5, v5, v82
	v_mul_f32_e32 v62, v62, v82
	v_mul_f32_e32 v63, v63, v82
	s_waitcnt lgkmcnt(0)
	v_fma_f32 v90, v90, v98, v94
	v_fma_f32 v91, v91, v99, v95
	v_fma_f32 v88, v88, v96, v92
	v_fma_f32 v89, v89, v97, v93
	v_mul_f32_e32 v92, v84, v82
	v_mul_f32_e32 v93, v85, v82
	v_cvt_pk_bf16_f32 v88, v88, v89
	v_cvt_pk_bf16_f32 v89, v90, v91
	global_store_dwordx2 v[58:59], v[88:89], off
	v_mul_f32_e32 v94, v86, v82
	v_mul_f32_e32 v95, v87, v82
	ds_read_b128 v[84:87], v83 offset:1024
	ds_read_b128 v[88:91], v83 offset:41984
	s_waitcnt lgkmcnt(0)
	v_fma_f32 v86, v86, v94, v90
	v_fma_f32 v87, v87, v95, v91
	v_fma_f32 v84, v84, v92, v88
	v_fma_f32 v85, v85, v93, v89
	v_mul_f32_e32 v88, v74, v82
	v_mul_f32_e32 v89, v75, v82
	v_cvt_pk_bf16_f32 v84, v84, v85
	v_cvt_pk_bf16_f32 v85, v86, v87
	global_store_dwordx2 v[58:59], v[84:85], off offset:512
	v_mul_f32_e32 v90, v76, v82
	v_mul_f32_e32 v91, v77, v82
	ds_read_b128 v[74:77], v83 offset:2048
	ds_read_b128 v[84:87], v83 offset:43008
	s_waitcnt lgkmcnt(0)
	v_fma_f32 v76, v76, v90, v86
	v_fma_f32 v77, v77, v91, v87
	v_fma_f32 v74, v74, v88, v84
	v_fma_f32 v75, v75, v89, v85
	v_mul_f32_e32 v84, v78, v82
	v_mul_f32_e32 v85, v79, v82
	v_cvt_pk_bf16_f32 v74, v74, v75
	v_cvt_pk_bf16_f32 v75, v76, v77
	global_store_dwordx2 v[58:59], v[74:75], off offset:1024
	v_mul_f32_e32 v86, v80, v82
	v_mul_f32_e32 v87, v81, v82
	ds_read_b128 v[74:77], v83 offset:3072
	ds_read_b128 v[78:81], v83 offset:44032
	s_waitcnt lgkmcnt(0)
	v_fma_f32 v76, v86, v76, v80
	v_fma_f32 v77, v87, v77, v81
	v_fma_f32 v74, v84, v74, v78
	v_fma_f32 v75, v85, v75, v79
	v_mul_f32_e32 v78, v66, v82
	v_mul_f32_e32 v79, v67, v82
	v_cvt_pk_bf16_f32 v74, v74, v75
	v_cvt_pk_bf16_f32 v75, v76, v77
	global_store_dwordx2 v[58:59], v[74:75], off offset:1536
	v_mul_f32_e32 v80, v68, v82
	v_mul_f32_e32 v81, v69, v82
	ds_read_b128 v[66:69], v83 offset:4096
	ds_read_b128 v[74:77], v83 offset:45056
	s_waitcnt lgkmcnt(0)
	v_fma_f32 v68, v80, v68, v76
	v_fma_f32 v69, v81, v69, v77
	v_fma_f32 v66, v78, v66, v74
	v_fma_f32 v67, v79, v67, v75
	v_mul_f32_e32 v74, v70, v82
	v_mul_f32_e32 v75, v71, v82
	v_cvt_pk_bf16_f32 v66, v66, v67
	v_cvt_pk_bf16_f32 v67, v68, v69
	global_store_dwordx2 v[58:59], v[66:67], off offset:2048
	v_mul_f32_e32 v76, v72, v82
	v_mul_f32_e32 v77, v73, v82
	ds_read_b128 v[66:69], v83 offset:5120
	ds_read_b128 v[70:73], v83 offset:46080
	s_waitcnt lgkmcnt(0)
; #define GAS __attribute__((address_space(1)))
; #define LAS __attribute__((address_space(3)))
; #define NR_LOAD(dst, k_) do { const GAS v2u* xr_ = (const GAS v2u*)(X + (size_t)(nw + 2048 * (k_)) * D) + F.lane; \
;         _Pragma("unroll") for (int j = 0; j < 8; ++j) dst[j] = __builtin_nontemporal_load(xr_ + 64 * j); } while (0)
; __device__ __forceinline__ void norm_mod_phase2(const Args& a, Frame& F, const float* gain, const float* modl, int sh_off, int sc_off, int nrows, const float* slab_gate) {
;     ...
;     NR_LOAD(r0, 0); NR_LOAD(r1, 1); NR_LOAD(r2, 2); NR_LOAD(r3, 3); NR_LOAD(r4, 4); NR_LOAD(r5, 5); NR_LOAD(r6, 6); NR_LOAD(r7, 7);
;     { const GAS f32x4* g4 = (const GAS f32x4*)gain;
;       for (int q = F.tid; q < 5 * D / 4; q += NWAVES * 64) { const int bq = q >> 9, cq = q & 511; const GAS f32x4* mb4 = (const GAS f32x4*)(modl + (size_t)bq * MOD_LD);
;           ((LAS f32x4*)CA)[q] = g4[cq] * (mb4[sc_off / 4 + cq] + 1.0f); ((LAS f32x4*)CB)[q] = mb4[sh_off / 4 + cq]; } }
;     asm volatile("s_waitcnt lgkmcnt(0)" ::: "memory"); __builtin_amdgcn_s_barrier(); asm volatile("" ::: "memory");
;     NR_FINISH(r0, nw,            (nw) >> 12);
;     NR_FINISH(r1, nw + 2048,     (nw + 2048) >> 12);
;     NR_FINISH(r2, nw + 2 * 2048, (nw + 2 * 2048) >> 12);
;     NR_FINISH(r3, nw + 3 * 2048, (nw + 3 * 2048) >> 12);
;     NR_FINISH(r4, nw + 4 * 2048, (nw + 4 * 2048) >> 12);
;     NR_FINISH(r5, nw + 5 * 2048, (nw + 5 * 2048) >> 12);
	v_fma_f32 v68, v76, v68, v72
	v_fma_f32 v69, v77, v69, v73
	v_fma_f32 v66, v74, v66, v70
	v_fma_f32 v67, v75, v67, v71
	s_waitcnt vmcnt(60)
	v_cvt_f32_f16_sdwa v75, v57 dst_sel:DWORD dst_unused:UNUSED_PAD src0_sel:WORD_1
	v_cvt_pk_bf16_f32 v66, v66, v67
	v_cvt_pk_bf16_f32 v67, v68, v69
	global_store_dwordx2 v[58:59], v[66:67], off offset:2560
	ds_read_b128 v[66:69], v83 offset:6144
	ds_read_b128 v[70:73], v83 offset:47104
	v_cvt_f32_f16_e32 v74, v57
	s_waitcnt lgkmcnt(0)
	v_fma_f32 v62, v62, v68, v72
	v_fma_f32 v63, v63, v69, v73
	v_fma_f32 v4, v4, v66, v70
	v_fma_f32 v5, v5, v67, v71
	v_mul_f32_e32 v68, v64, v82
	v_mul_f32_e32 v69, v65, v82
	v_cvt_pk_bf16_f32 v4, v4, v5
	v_cvt_pk_bf16_f32 v5, v62, v63
	global_store_dwordx2 v[58:59], v[4:5], off offset:3072
	v_mul_f32_e32 v4, v60, v82
	v_mul_f32_e32 v5, v61, v82
	ds_read_b128 v[60:63], v83 offset:7168
	ds_read_b128 v[64:67], v83 offset:48128
	v_cvt_f32_f16_sdwa v73, v56 dst_sel:DWORD dst_unused:UNUSED_PAD src0_sel:WORD_1
	v_cvt_f32_f16_e32 v72, v56
	s_waitcnt vmcnt(61)
	v_cvt_f32_f16_sdwa v71, v55 dst_sel:DWORD dst_unused:UNUSED_PAD src0_sel:WORD_1
	v_cvt_f32_f16_e32 v70, v55
	s_waitcnt lgkmcnt(0)
	v_fma_f32 v62, v68, v62, v66
	v_fma_f32 v63, v69, v63, v67
	v_cvt_f32_f16_sdwa v69, v54 dst_sel:DWORD dst_unused:UNUSED_PAD src0_sel:WORD_1
	v_cvt_f32_f16_e32 v68, v54
	v_fma_f32 v4, v4, v60, v64
	v_fma_f32 v5, v5, v61, v65
	v_mov_b32_e32 v54, v73
	v_cvt_pk_bf16_f32 v4, v4, v5
	v_cvt_pk_bf16_f32 v5, v62, v63
	global_store_dwordx2 v[58:59], v[4:5], off offset:3584
	v_mov_b32_e32 v55, v69
	s_waitcnt vmcnt(61)
	v_cvt_f32_f16_sdwa v59, v52 dst_sel:DWORD dst_unused:UNUSED_PAD src0_sel:WORD_1
	v_cvt_f32_f16_sdwa v61, v53 dst_sel:DWORD dst_unused:UNUSED_PAD src0_sel:WORD_1
	v_mov_b32_e32 v4, v72
	v_mov_b32_e32 v5, v68
	v_mul_f32_e32 v54, v54, v54
	v_mul_f32_e32 v55, v55, v55
	v_mov_b32_e32 v56, v75
	v_mov_b32_e32 v57, v71
	v_cvt_f32_f16_e32 v58, v52
	v_cvt_f32_f16_e32 v60, v53
	s_waitcnt vmcnt(60)
	v_cvt_f32_f16_sdwa v63, v50 dst_sel:DWORD dst_unused:UNUSED_PAD src0_sel:WORD_1
	v_fma_f32 v4, v4, v4, v54
	v_fma_f32 v5, v5, v5, v55
	v_mov_b32_e32 v54, v74
	v_mov_b32_e32 v55, v70
	v_mul_f32_e32 v56, v56, v56
	v_mul_f32_e32 v57, v57, v57
	v_cvt_f32_f16_e32 v62, v50
	v_cvt_f32_f16_sdwa v65, v51 dst_sel:DWORD dst_unused:UNUSED_PAD src0_sel:WORD_1
	v_fma_f32 v54, v54, v54, v56
	v_fma_f32 v55, v55, v55, v57
	v_cvt_f32_f16_e32 v64, v51
	v_add_f32_e32 v4, v4, v54
	v_add_f32_e32 v5, v5, v55
	v_mov_b32_e32 v54, v59
	v_mov_b32_e32 v55, v61
	v_mov_b32_e32 v52, v58
	v_mov_b32_e32 v53, v60
	v_mul_f32_e32 v54, v54, v54
	v_mul_f32_e32 v55, v55, v55
	v_mul_f32_e32 v50, v63, v63
	v_fma_f32 v52, v52, v52, v54
	v_fma_f32 v53, v53, v53, v55
	v_fma_f32 v56, v62, v62, v50
	v_fma_f32 v57, v63, v63, v50
	v_mul_f32_e32 v50, v65, v65
	v_add_f32_e32 v54, v52, v53
	v_add_f32_e32 v55, v53, v52
	v_fma_f32 v66, v64, v64, v50
	v_fma_f32 v67, v65, v65, v50
	s_waitcnt vmcnt(59)
	v_cvt_f32_f16_sdwa v51, v48 dst_sel:DWORD dst_unused:UNUSED_PAD src0_sel:WORD_1
	v_cvt_f32_f16_e32 v50, v48
	v_cvt_f32_f16_sdwa v53, v49 dst_sel:DWORD dst_unused:UNUSED_PAD src0_sel:WORD_1
	v_cvt_f32_f16_e32 v52, v49
	v_pk_add_f32 v[4:5], v[4:5], v[4:5] op_sel:[0,1] op_sel_hi:[1,0]
	v_mul_f32_e32 v48, v50, v50
	v_mul_f32_e32 v49, v51, v51
	v_mul_f32_e32 v76, v52, v52
	v_mul_f32_e32 v77, v53, v53
	v_mov_b32_e32 v5, v48
	v_mov_b32_e32 v55, v49
	v_mov_b32_e32 v57, v76
	v_mov_b32_e32 v67, v77
	v_add_f32_e32 v4, v4, v54
	v_add_f32_e32 v5, v5, v55
	v_add_f32_e32 v48, v56, v66
	v_add_f32_e32 v49, v57, v67
	s_waitcnt vmcnt(58)
	v_cvt_f32_f16_sdwa v55, v46 dst_sel:DWORD dst_unused:UNUSED_PAD src0_sel:WORD_1
	v_cvt_f32_f16_sdwa v57, v47 dst_sel:DWORD dst_unused:UNUSED_PAD src0_sel:WORD_1
	v_cvt_f32_f16_e32 v54, v46
	v_cvt_f32_f16_e32 v56, v47
	v_add_f32_e32 v4, v4, v48
	v_add_f32_e32 v5, v5, v49
	v_mov_b32_e32 v46, v55
	v_mov_b32_e32 v47, v57
	v_add_f32_e32 v66, v4, v5
	v_add_f32_e32 v67, v5, v4
	v_mov_b32_e32 v4, v54
	v_mov_b32_e32 v5, v56
	v_mul_f32_e32 v46, v46, v46
	v_mul_f32_e32 v47, v47, v47
	s_waitcnt vmcnt(56)
	v_cvt_f32_f16_sdwa v49, v43 dst_sel:DWORD dst_unused:UNUSED_PAD src0_sel:WORD_1
	v_fma_f32 v4, v4, v4, v46
	v_fma_f32 v5, v5, v5, v47
	v_cvt_f32_f16_sdwa v47, v45 dst_sel:DWORD dst_unused:UNUSED_PAD src0_sel:WORD_1
	v_add_f32_e32 v76, v4, v5
	v_add_f32_e32 v77, v5, v4
	v_cvt_f32_f16_sdwa v5, v44 dst_sel:DWORD dst_unused:UNUSED_PAD src0_sel:WORD_1
	v_cvt_f32_f16_e32 v4, v44
	v_cvt_f32_f16_e32 v46, v45
	v_cvt_f32_f16_e32 v48, v43
	v_mul_f32_e32 v44, v5, v5
	v_fma_f32 v78, v4, v4, v44
	v_fma_f32 v79, v5, v5, v44
	v_mul_f32_e32 v44, v47, v47
	v_fma_f32 v80, v46, v46, v44
	v_fma_f32 v81, v47, v47, v44
	v_cvt_f32_f16_sdwa v45, v42 dst_sel:DWORD dst_unused:UNUSED_PAD src0_sel:WORD_1
	v_cvt_f32_f16_e32 v44, v42
	v_mul_f32_e32 v82, v48, v48
	v_mul_f32_e32 v83, v49, v49
	v_mul_f32_e32 v42, v44, v44
	v_mul_f32_e32 v43, v45, v45
	s_nop 0
	v_mov_b32_e32 v67, v42
	v_mov_b32_e32 v77, v43
	v_mov_b32_e32 v79, v82
	v_mov_b32_e32 v81, v83
	v_add_f32_e32 v42, v66, v76
	v_add_f32_e32 v43, v67, v77
	v_add_f32_e32 v66, v78, v80
	v_add_f32_e32 v67, v79, v81
	s_nop 0
	v_add_f32_e32 v42, v42, v66
	v_add_f32_e32 v43, v43, v67
	s_nop 0
	v_add_f32_e32 v42, v42, v43
	s_nop 1
	v_add_f32_dpp v42, v42, v42 quad_perm:[1,0,3,2] row_mask:0xf bank_mask:0xf bound_ctrl:1
	s_nop 1
	v_add_f32_dpp v42, v42, v42 quad_perm:[2,3,0,1] row_mask:0xf bank_mask:0xf bound_ctrl:1
	s_nop 1
	v_add_f32_dpp v42, v42, v42 row_half_mirror row_mask:0xf bank_mask:0xf bound_ctrl:1
	s_nop 1
	v_add_f32_dpp v42, v42, v42 row_mirror row_mask:0xf bank_mask:0xf bound_ctrl:1
	s_nop 0
	v_readlane_b32 s8, v42, 16
; #define GAS __attribute__((address_space(1)))
; #define LAS __attribute__((address_space(3)))
; #define NR_LOAD(dst, k_) do { const GAS v2u* xr_ = (const GAS v2u*)(X + (size_t)(nw + 2048 * (k_)) * D) + F.lane; \
;         _Pragma("unroll") for (int j = 0; j < 8; ++j) dst[j] = __builtin_nontemporal_load(xr_ + 64 * j); } while (0)
; __device__ __forceinline__ void norm_mod_phase2(const Args& a, Frame& F, const float* gain, const float* modl, int sh_off, int sc_off, int nrows, const float* slab_gate) {
;     ...
;     NR_LOAD(r0, 0); NR_LOAD(r1, 1); NR_LOAD(r2, 2); NR_LOAD(r3, 3); NR_LOAD(r4, 4); NR_LOAD(r5, 5); NR_LOAD(r6, 6); NR_LOAD(r7, 7);
;     { const GAS f32x4* g4 = (const GAS f32x4*)gain;
;       for (int q = F.tid; q < 5 * D / 4; q += NWAVES * 64) { const int bq = q >> 9, cq = q & 511; const GAS f32x4* mb4 = (const GAS f32x4*)(modl + (size_t)bq * MOD_LD);
;           ((LAS f32x4*)CA)[q] = g4[cq] * (mb4[sc_off / 4 + cq] + 1.0f); ((LAS f32x4*)CB)[q] = mb4[sh_off / 4 + cq]; } }
;     asm volatile("s_waitcnt lgkmcnt(0)" ::: "memory"); __builtin_amdgcn_s_barrier(); asm volatile("" ::: "memory");
;     NR_FINISH(r0, nw,            (nw) >> 12);
;     NR_FINISH(r1, nw + 2048,     (nw + 2048) >> 12);
;     NR_FINISH(r2, nw + 2 * 2048, (nw + 2 * 2048) >> 12);
;     NR_FINISH(r3, nw + 3 * 2048, (nw + 3 * 2048) >> 12);
;     NR_FINISH(r4, nw + 4 * 2048, (nw + 4 * 2048) >> 12);
;     NR_FINISH(r5, nw + 5 * 2048, (nw + 5 * 2048) >> 12);
	v_readlane_b32 s9, v42, 48
	v_readlane_b32 s6, v42, 0
	v_readlane_b32 s7, v42, 32
	v_mov_b32_e32 v42, s8
	v_mov_b32_e32 v43, s9
	v_add_f32_e32 v42, s6, v42
	v_add_f32_e32 v43, s7, v43
	s_nop 0
	v_add_f32_e32 v42, v42, v43
	v_fmamk_f32 v42, v42, 0x3a000000, v252
	v_cmp_gt_f32_e32 vcc, s55, v42
	v_mul_f32_e32 v43, 0x4f800000, v42
	s_nop 0
	v_cndmask_b32_e32 v42, v42, v43, vcc
	v_sqrt_f32_e32 v43, v42
	s_nop 0
	v_add_u32_e32 v66, -1, v43
	v_fma_f32 v67, -v66, v43, v42
	v_cmp_ge_f32_e64 s[8:9], 0, v67
	v_add_u32_e32 v67, 1, v43
	s_nop 0
	v_cndmask_b32_e64 v66, v43, v66, s[8:9]
	v_fma_f32 v43, -v67, v43, v42
	v_cmp_lt_f32_e64 s[8:9], 0, v43
	s_nop 1
	v_cndmask_b32_e64 v43, v66, v67, s[8:9]
	v_mul_f32_e32 v66, 0x37800000, v43
	v_cndmask_b32_e32 v43, v43, v66, vcc
	v_cmp_class_f32_e32 vcc, v42, v253
	s_nop 1
	v_cndmask_b32_e32 v42, v43, v42, vcc
	v_div_scale_f32 v43, s[6:7], v42, v42, 1.0
	v_rcp_f32_e32 v66, v43
	s_lshl_b32 s6, s22, 1
	s_and_b32 s6, s6, 0xffffe000
	s_add_i32 s6, s6, 0
	v_fma_f32 v67, -v43, v66, 1.0
	v_fmac_f32_e32 v66, v67, v66
	v_div_scale_f32 v67, vcc, 1.0, v42, 1.0
	v_mul_f32_e32 v76, v67, v66
	v_fma_f32 v77, -v43, v76, v67
	v_fmac_f32_e32 v76, v77, v66
	v_fma_f32 v43, -v43, v76, v67
	v_div_fmas_f32 v43, v43, v66, v76
	v_div_fixup_f32 v66, v43, v42, 1.0
	v_mul_f32_e32 v80, v72, v66
	v_mul_f32_e32 v81, v73, v66
	v_mul_f32_e32 v82, v74, v66
	v_mul_f32_e32 v83, v75, v66
	v_add_u32_e32 v67, s6, v0
	ds_read_b128 v[72:75], v67
	ds_read_b128 v[76:79], v67 offset:40960
	v_lshl_add_u64 v[42:43], s[24:25], 1, v[2:3]
	v_lshl_add_u64 v[42:43], v[42:43], 0, v[6:7]
	v_mul_f32_e32 v4, v4, v66
	v_mul_f32_e32 v5, v5, v66
	v_mul_f32_e32 v46, v46, v66
	v_mul_f32_e32 v47, v47, v66
	s_waitcnt lgkmcnt(0)
	v_fma_f32 v74, v74, v82, v78
	v_fma_f32 v75, v75, v83, v79
	v_fma_f32 v72, v72, v80, v76
	v_fma_f32 v73, v73, v81, v77
	v_mul_f32_e32 v76, v68, v66
	v_mul_f32_e32 v77, v69, v66
	v_cvt_pk_bf16_f32 v72, v72, v73
	v_cvt_pk_bf16_f32 v73, v74, v75
	global_store_dwordx2 v[42:43], v[72:73], off
	v_mul_f32_e32 v78, v70, v66
	v_mul_f32_e32 v79, v71, v66
	ds_read_b128 v[68:71], v67 offset:1024
	ds_read_b128 v[72:75], v67 offset:41984
	s_waitcnt lgkmcnt(0)
	v_fma_f32 v70, v70, v78, v74
	v_fma_f32 v71, v71, v79, v75
	v_fma_f32 v68, v68, v76, v72
	v_fma_f32 v69, v69, v77, v73
	v_mul_f32_e32 v72, v58, v66
	v_mul_f32_e32 v73, v59, v66
	v_cvt_pk_bf16_f32 v68, v68, v69
	v_cvt_pk_bf16_f32 v69, v70, v71
	global_store_dwordx2 v[42:43], v[68:69], off offset:512
	v_mul_f32_e32 v74, v60, v66
	v_mul_f32_e32 v75, v61, v66
	ds_read_b128 v[58:61], v67 offset:2048
	ds_read_b128 v[68:71], v67 offset:43008
	s_waitcnt lgkmcnt(0)
	v_fma_f32 v60, v60, v74, v70
	v_fma_f32 v61, v61, v75, v71
	v_fma_f32 v58, v58, v72, v68
	v_fma_f32 v59, v59, v73, v69
	v_mul_f32_e32 v68, v62, v66
	v_mul_f32_e32 v69, v63, v66
	v_cvt_pk_bf16_f32 v58, v58, v59
	v_cvt_pk_bf16_f32 v59, v60, v61
	global_store_dwordx2 v[42:43], v[58:59], off offset:1024
	v_mul_f32_e32 v70, v64, v66
	v_mul_f32_e32 v71, v65, v66
	ds_read_b128 v[58:61], v67 offset:3072
	ds_read_b128 v[62:65], v67 offset:44032
	s_waitcnt lgkmcnt(0)
	v_fma_f32 v60, v70, v60, v64
	v_fma_f32 v61, v71, v61, v65
	v_fma_f32 v58, v68, v58, v62
	v_fma_f32 v59, v69, v59, v63
	v_mul_f32_e32 v62, v50, v66
	v_mul_f32_e32 v63, v51, v66
	v_cvt_pk_bf16_f32 v58, v58, v59
	v_cvt_pk_bf16_f32 v59, v60, v61
	global_store_dwordx2 v[42:43], v[58:59], off offset:1536
	v_mul_f32_e32 v64, v52, v66
	v_mul_f32_e32 v65, v53, v66
	ds_read_b128 v[50:53], v67 offset:4096
	ds_read_b128 v[58:61], v67 offset:45056
	s_waitcnt lgkmcnt(0)
	v_fma_f32 v52, v64, v52, v60
	v_fma_f32 v53, v65, v53, v61
	v_fma_f32 v50, v62, v50, v58
	v_fma_f32 v51, v63, v51, v59
	v_mul_f32_e32 v58, v54, v66
	v_mul_f32_e32 v59, v55, v66
	v_cvt_pk_bf16_f32 v50, v50, v51
	v_cvt_pk_bf16_f32 v51, v52, v53
	global_store_dwordx2 v[42:43], v[50:51], off offset:2048
	v_mul_f32_e32 v60, v56, v66
	v_mul_f32_e32 v61, v57, v66
	ds_read_b128 v[50:53], v67 offset:5120
	ds_read_b128 v[54:57], v67 offset:46080
	s_waitcnt lgkmcnt(0)
	v_fma_f32 v52, v60, v52, v56
	v_fma_f32 v53, v61, v53, v57
	v_fma_f32 v50, v58, v50, v54
	v_fma_f32 v51, v59, v51, v55
	s_waitcnt vmcnt(60)
	v_cvt_f32_f16_sdwa v59, v41 dst_sel:DWORD dst_unused:UNUSED_PAD src0_sel:WORD_1
	v_cvt_pk_bf16_f32 v50, v50, v51
	v_cvt_pk_bf16_f32 v51, v52, v53
	global_store_dwordx2 v[42:43], v[50:51], off offset:2560
	ds_read_b128 v[50:53], v67 offset:6144
	ds_read_b128 v[54:57], v67 offset:47104
	v_cvt_f32_f16_e32 v58, v41
	s_waitcnt lgkmcnt(0)
	v_fma_f32 v46, v46, v52, v56
	v_fma_f32 v47, v47, v53, v57
	v_fma_f32 v4, v4, v50, v54
	v_fma_f32 v5, v5, v51, v55
	v_mul_f32_e32 v52, v48, v66
	v_mul_f32_e32 v53, v49, v66
	v_cvt_pk_bf16_f32 v4, v4, v5
	v_cvt_pk_bf16_f32 v5, v46, v47
	global_store_dwordx2 v[42:43], v[4:5], off offset:3072
	v_mul_f32_e32 v4, v44, v66
	v_mul_f32_e32 v5, v45, v66
	ds_read_b128 v[44:47], v67 offset:7168
	ds_read_b128 v[48:51], v67 offset:48128
	v_cvt_f32_f16_sdwa v57, v40 dst_sel:DWORD dst_unused:UNUSED_PAD src0_sel:WORD_1
	v_cvt_f32_f16_e32 v56, v40
	s_waitcnt vmcnt(61)
	v_cvt_f32_f16_sdwa v55, v39 dst_sel:DWORD dst_unused:UNUSED_PAD src0_sel:WORD_1
	v_cvt_f32_f16_e32 v54, v39
	s_waitcnt lgkmcnt(0)
	v_fma_f32 v46, v52, v46, v50
	v_fma_f32 v47, v53, v47, v51
	v_cvt_f32_f16_sdwa v53, v38 dst_sel:DWORD dst_unused:UNUSED_PAD src0_sel:WORD_1
	v_cvt_f32_f16_e32 v52, v38
	v_fma_f32 v4, v4, v44, v48
	v_fma_f32 v5, v5, v45, v49
	v_mov_b32_e32 v38, v57
	v_cvt_pk_bf16_f32 v4, v4, v5
	v_cvt_pk_bf16_f32 v5, v46, v47
	global_store_dwordx2 v[42:43], v[4:5], off offset:3584
	v_mov_b32_e32 v39, v53
	s_waitcnt vmcnt(61)
; #define GAS __attribute__((address_space(1)))
; #define LAS __attribute__((address_space(3)))
; #define NR_LOAD(dst, k_) do { const GAS v2u* xr_ = (const GAS v2u*)(X + (size_t)(nw + 2048 * (k_)) * D) + F.lane; \
;         _Pragma("unroll") for (int j = 0; j < 8; ++j) dst[j] = __builtin_nontemporal_load(xr_ + 64 * j); } while (0)
; __device__ __forceinline__ void norm_mod_phase2(const Args& a, Frame& F, const float* gain, const float* modl, int sh_off, int sc_off, int nrows, const float* slab_gate) {
;     ...
;     NR_LOAD(r0, 0); NR_LOAD(r1, 1); NR_LOAD(r2, 2); NR_LOAD(r3, 3); NR_LOAD(r4, 4); NR_LOAD(r5, 5); NR_LOAD(r6, 6); NR_LOAD(r7, 7);
;     { const GAS f32x4* g4 = (const GAS f32x4*)gain;
;       for (int q = F.tid; q < 5 * D / 4; q += NWAVES * 64) { const int bq = q >> 9, cq = q & 511; const GAS f32x4* mb4 = (const GAS f32x4*)(modl + (size_t)bq * MOD_LD);
;           ((LAS f32x4*)CA)[q] = g4[cq] * (mb4[sc_off / 4 + cq] + 1.0f); ((LAS f32x4*)CB)[q] = mb4[sh_off / 4 + cq]; } }
;     asm volatile("s_waitcnt lgkmcnt(0)" ::: "memory"); __builtin_amdgcn_s_barrier(); asm volatile("" ::: "memory");
;     NR_FINISH(r0, nw,            (nw) >> 12);
;     NR_FINISH(r1, nw + 2048,     (nw + 2048) >> 12);
;     NR_FINISH(r2, nw + 2 * 2048, (nw + 2 * 2048) >> 12);
;     NR_FINISH(r3, nw + 3 * 2048, (nw + 3 * 2048) >> 12);
;     NR_FINISH(r4, nw + 4 * 2048, (nw + 4 * 2048) >> 12);
;     NR_FINISH(r5, nw + 5 * 2048, (nw + 5 * 2048) >> 12);
;     NR_FINISH(r6, nw + 6 * 2048, (nw + 6 * 2048) >> 12);
	v_cvt_f32_f16_sdwa v43, v36 dst_sel:DWORD dst_unused:UNUSED_PAD src0_sel:WORD_1
	v_cvt_f32_f16_sdwa v45, v37 dst_sel:DWORD dst_unused:UNUSED_PAD src0_sel:WORD_1
	v_mov_b32_e32 v4, v56
	v_mov_b32_e32 v5, v52
	v_mul_f32_e32 v38, v38, v38
	v_mul_f32_e32 v39, v39, v39
	v_mov_b32_e32 v40, v59
	v_mov_b32_e32 v41, v55
	v_cvt_f32_f16_e32 v42, v36
	v_cvt_f32_f16_e32 v44, v37
	s_waitcnt vmcnt(60)
	v_cvt_f32_f16_sdwa v47, v34 dst_sel:DWORD dst_unused:UNUSED_PAD src0_sel:WORD_1
	v_fma_f32 v4, v4, v4, v38
	v_fma_f32 v5, v5, v5, v39
	v_mov_b32_e32 v38, v58
	v_mov_b32_e32 v39, v54
	v_mul_f32_e32 v40, v40, v40
	v_mul_f32_e32 v41, v41, v41
	v_cvt_f32_f16_e32 v46, v34
	v_cvt_f32_f16_sdwa v49, v35 dst_sel:DWORD dst_unused:UNUSED_PAD src0_sel:WORD_1
	v_fma_f32 v38, v38, v38, v40
	v_fma_f32 v39, v39, v39, v41
	v_cvt_f32_f16_e32 v48, v35
	v_add_f32_e32 v4, v4, v38
	v_add_f32_e32 v5, v5, v39
	v_mov_b32_e32 v38, v43
	v_mov_b32_e32 v39, v45
	v_mov_b32_e32 v36, v42
	v_mov_b32_e32 v37, v44
	v_mul_f32_e32 v38, v38, v38
	v_mul_f32_e32 v39, v39, v39
	v_mul_f32_e32 v34, v47, v47
	v_fma_f32 v36, v36, v36, v38
	v_fma_f32 v37, v37, v37, v39
	v_fma_f32 v40, v46, v46, v34
	v_fma_f32 v41, v47, v47, v34
	v_mul_f32_e32 v34, v49, v49
	v_add_f32_e32 v38, v36, v37
	v_add_f32_e32 v39, v37, v36
	v_fma_f32 v50, v48, v48, v34
	v_fma_f32 v51, v49, v49, v34
	s_waitcnt vmcnt(59)
	v_cvt_f32_f16_sdwa v35, v32 dst_sel:DWORD dst_unused:UNUSED_PAD src0_sel:WORD_1
	v_cvt_f32_f16_e32 v34, v32
	v_cvt_f32_f16_sdwa v37, v33 dst_sel:DWORD dst_unused:UNUSED_PAD src0_sel:WORD_1
	v_cvt_f32_f16_e32 v36, v33
	v_pk_add_f32 v[4:5], v[4:5], v[4:5] op_sel:[0,1] op_sel_hi:[1,0]
	v_mul_f32_e32 v32, v34, v34
	v_mul_f32_e32 v33, v35, v35
	v_mul_f32_e32 v60, v36, v36
	v_mul_f32_e32 v61, v37, v37
	v_mov_b32_e32 v5, v32
	v_mov_b32_e32 v39, v33
	v_mov_b32_e32 v41, v60
	v_mov_b32_e32 v51, v61
	v_add_f32_e32 v4, v4, v38
	v_add_f32_e32 v5, v5, v39
	v_add_f32_e32 v32, v40, v50
	v_add_f32_e32 v33, v41, v51
	s_waitcnt vmcnt(58)
	v_cvt_f32_f16_sdwa v39, v30 dst_sel:DWORD dst_unused:UNUSED_PAD src0_sel:WORD_1
	v_cvt_f32_f16_sdwa v41, v31 dst_sel:DWORD dst_unused:UNUSED_PAD src0_sel:WORD_1
	v_cvt_f32_f16_e32 v38, v30
	v_cvt_f32_f16_e32 v40, v31
	v_add_f32_e32 v4, v4, v32
	v_add_f32_e32 v5, v5, v33
	v_mov_b32_e32 v30, v39
	v_mov_b32_e32 v31, v41
	v_add_f32_e32 v50, v4, v5
	v_add_f32_e32 v51, v5, v4
	v_mov_b32_e32 v4, v38
	v_mov_b32_e32 v5, v40
	v_mul_f32_e32 v30, v30, v30
	v_mul_f32_e32 v31, v31, v31
	s_waitcnt vmcnt(56)
	v_cvt_f32_f16_sdwa v33, v27 dst_sel:DWORD dst_unused:UNUSED_PAD src0_sel:WORD_1
	v_fma_f32 v4, v4, v4, v30
	v_fma_f32 v5, v5, v5, v31
	v_cvt_f32_f16_sdwa v31, v29 dst_sel:DWORD dst_unused:UNUSED_PAD src0_sel:WORD_1
	v_add_f32_e32 v60, v4, v5
	v_add_f32_e32 v61, v5, v4
	v_cvt_f32_f16_sdwa v5, v28 dst_sel:DWORD dst_unused:UNUSED_PAD src0_sel:WORD_1
	v_cvt_f32_f16_e32 v4, v28
	v_cvt_f32_f16_e32 v30, v29
	v_cvt_f32_f16_e32 v32, v27
	v_mul_f32_e32 v28, v5, v5
	v_fma_f32 v62, v4, v4, v28
	v_fma_f32 v63, v5, v5, v28
	v_mul_f32_e32 v28, v31, v31
	v_fma_f32 v64, v30, v30, v28
	v_fma_f32 v65, v31, v31, v28
	v_cvt_f32_f16_sdwa v29, v26 dst_sel:DWORD dst_unused:UNUSED_PAD src0_sel:WORD_1
	v_cvt_f32_f16_e32 v28, v26
	v_mul_f32_e32 v66, v32, v32
	v_mul_f32_e32 v67, v33, v33
	v_mul_f32_e32 v26, v28, v28
	v_mul_f32_e32 v27, v29, v29
	s_nop 0
	v_mov_b32_e32 v51, v26
	v_mov_b32_e32 v61, v27
	v_mov_b32_e32 v63, v66
	v_mov_b32_e32 v65, v67
	v_add_f32_e32 v26, v50, v60
	v_add_f32_e32 v27, v51, v61
	v_add_f32_e32 v50, v62, v64
	v_add_f32_e32 v51, v63, v65
	s_nop 0
	v_add_f32_e32 v26, v26, v50
	v_add_f32_e32 v27, v27, v51
	s_nop 0
	v_add_f32_e32 v26, v26, v27
	s_nop 1
	v_add_f32_dpp v26, v26, v26 quad_perm:[1,0,3,2] row_mask:0xf bank_mask:0xf bound_ctrl:1
	s_nop 1
	v_add_f32_dpp v26, v26, v26 quad_perm:[2,3,0,1] row_mask:0xf bank_mask:0xf bound_ctrl:1
	s_nop 1
	v_add_f32_dpp v26, v26, v26 row_half_mirror row_mask:0xf bank_mask:0xf bound_ctrl:1
	s_nop 1
	v_add_f32_dpp v26, v26, v26 row_mirror row_mask:0xf bank_mask:0xf bound_ctrl:1
	s_nop 0
	v_readlane_b32 s8, v26, 16
	v_readlane_b32 s9, v26, 48
	v_readlane_b32 s6, v26, 0
	v_readlane_b32 s7, v26, 32
	v_mov_b32_e32 v26, s8
	v_mov_b32_e32 v27, s9
	v_add_f32_e32 v26, s6, v26
	v_add_f32_e32 v27, s7, v27
	s_nop 0
	v_add_f32_e32 v26, v26, v27
	v_fmamk_f32 v26, v26, 0x3a000000, v252
	v_cmp_gt_f32_e32 vcc, s55, v26
	v_mul_f32_e32 v27, 0x4f800000, v26
	s_nop 0
	v_cndmask_b32_e32 v26, v26, v27, vcc
	v_sqrt_f32_e32 v27, v26
	s_nop 0
	v_add_u32_e32 v50, -1, v27
	v_fma_f32 v51, -v50, v27, v26
	v_cmp_ge_f32_e64 s[8:9], 0, v51
	v_add_u32_e32 v51, 1, v27
	s_nop 0
	v_cndmask_b32_e64 v50, v27, v50, s[8:9]
	v_fma_f32 v27, -v51, v27, v26
	v_cmp_lt_f32_e64 s[8:9], 0, v27
	s_nop 1
	v_cndmask_b32_e64 v27, v50, v51, s[8:9]
	v_mul_f32_e32 v50, 0x37800000, v27
	v_cndmask_b32_e32 v27, v27, v50, vcc
	v_cmp_class_f32_e32 vcc, v26, v253
	s_nop 1
	v_cndmask_b32_e32 v26, v27, v26, vcc
	v_div_scale_f32 v27, s[6:7], v26, v26, 1.0
	v_rcp_f32_e32 v50, v27
	s_lshl_b32 s6, s18, 1
	s_and_b32 s6, s6, 0xffffe000
	s_add_i32 s6, s6, 0
	v_fma_f32 v51, -v27, v50, 1.0
	v_fmac_f32_e32 v50, v51, v50
	v_div_scale_f32 v51, vcc, 1.0, v26, 1.0
	v_mul_f32_e32 v60, v51, v50
	v_fma_f32 v61, -v27, v60, v51
	v_fmac_f32_e32 v60, v61, v50
	v_fma_f32 v27, -v27, v60, v51
	v_div_fmas_f32 v27, v27, v50, v60
	v_div_fixup_f32 v50, v27, v26, 1.0
	v_mul_f32_e32 v64, v56, v50
	v_mul_f32_e32 v65, v57, v50
	v_mul_f32_e32 v66, v58, v50
	v_mul_f32_e32 v67, v59, v50
	v_add_u32_e32 v51, s6, v0
	ds_read_b128 v[56:59], v51
	ds_read_b128 v[60:63], v51 offset:40960
	v_lshl_add_u64 v[26:27], s[20:21], 1, v[2:3]
	v_lshl_add_u64 v[26:27], v[26:27], 0, v[6:7]
	v_mul_f32_e32 v4, v4, v50
	v_mul_f32_e32 v5, v5, v50
	v_mul_f32_e32 v30, v30, v50
	v_mul_f32_e32 v31, v31, v50
	s_waitcnt lgkmcnt(0)
; #define GAS __attribute__((address_space(1)))
; #define LAS __attribute__((address_space(3)))
; #define NR_LOAD(dst, k_) do { const GAS v2u* xr_ = (const GAS v2u*)(X + (size_t)(nw + 2048 * (k_)) * D) + F.lane; \
;         _Pragma("unroll") for (int j = 0; j < 8; ++j) dst[j] = __builtin_nontemporal_load(xr_ + 64 * j); } while (0)
; __device__ __forceinline__ void norm_mod_phase2(const Args& a, Frame& F, const float* gain, const float* modl, int sh_off, int sc_off, int nrows, const float* slab_gate) {
;     ...
;     NR_LOAD(r0, 0); NR_LOAD(r1, 1); NR_LOAD(r2, 2); NR_LOAD(r3, 3); NR_LOAD(r4, 4); NR_LOAD(r5, 5); NR_LOAD(r6, 6); NR_LOAD(r7, 7);
;     { const GAS f32x4* g4 = (const GAS f32x4*)gain;
;       for (int q = F.tid; q < 5 * D / 4; q += NWAVES * 64) { const int bq = q >> 9, cq = q & 511; const GAS f32x4* mb4 = (const GAS f32x4*)(modl + (size_t)bq * MOD_LD);
;           ((LAS f32x4*)CA)[q] = g4[cq] * (mb4[sc_off / 4 + cq] + 1.0f); ((LAS f32x4*)CB)[q] = mb4[sh_off / 4 + cq]; } }
;     asm volatile("s_waitcnt lgkmcnt(0)" ::: "memory"); __builtin_amdgcn_s_barrier(); asm volatile("" ::: "memory");
;     NR_FINISH(r0, nw,            (nw) >> 12);
;     NR_FINISH(r1, nw + 2048,     (nw + 2048) >> 12);
;     NR_FINISH(r2, nw + 2 * 2048, (nw + 2 * 2048) >> 12);
;     NR_FINISH(r3, nw + 3 * 2048, (nw + 3 * 2048) >> 12);
;     NR_FINISH(r4, nw + 4 * 2048, (nw + 4 * 2048) >> 12);
;     NR_FINISH(r5, nw + 5 * 2048, (nw + 5 * 2048) >> 12);
;     NR_FINISH(r6, nw + 6 * 2048, (nw + 6 * 2048) >> 12);
;     NR_FINISH(r7, nw + 7 * 2048, (nw + 7 * 2048) >> 12);
	v_fma_f32 v58, v58, v66, v62
	v_fma_f32 v59, v59, v67, v63
	v_fma_f32 v56, v56, v64, v60
	v_fma_f32 v57, v57, v65, v61
	v_mul_f32_e32 v60, v52, v50
	v_mul_f32_e32 v61, v53, v50
	v_cvt_pk_bf16_f32 v56, v56, v57
	v_cvt_pk_bf16_f32 v57, v58, v59
	global_store_dwordx2 v[26:27], v[56:57], off
	v_mul_f32_e32 v62, v54, v50
	v_mul_f32_e32 v63, v55, v50
	ds_read_b128 v[52:55], v51 offset:1024
	ds_read_b128 v[56:59], v51 offset:41984
	s_waitcnt lgkmcnt(0)
	v_fma_f32 v54, v54, v62, v58
	v_fma_f32 v55, v55, v63, v59
	v_fma_f32 v52, v52, v60, v56
	v_fma_f32 v53, v53, v61, v57
	v_mul_f32_e32 v56, v42, v50
	v_mul_f32_e32 v57, v43, v50
	v_cvt_pk_bf16_f32 v52, v52, v53
	v_cvt_pk_bf16_f32 v53, v54, v55
	global_store_dwordx2 v[26:27], v[52:53], off offset:512
	v_mul_f32_e32 v58, v44, v50
	v_mul_f32_e32 v59, v45, v50
	ds_read_b128 v[42:45], v51 offset:2048
	ds_read_b128 v[52:55], v51 offset:43008
	s_waitcnt lgkmcnt(0)
	v_fma_f32 v44, v44, v58, v54
	v_fma_f32 v45, v45, v59, v55
	v_fma_f32 v42, v42, v56, v52
	v_fma_f32 v43, v43, v57, v53
	v_mul_f32_e32 v52, v46, v50
	v_mul_f32_e32 v53, v47, v50
	v_cvt_pk_bf16_f32 v42, v42, v43
	v_cvt_pk_bf16_f32 v43, v44, v45
	global_store_dwordx2 v[26:27], v[42:43], off offset:1024
	v_mul_f32_e32 v54, v48, v50
	v_mul_f32_e32 v55, v49, v50
	ds_read_b128 v[42:45], v51 offset:3072
	ds_read_b128 v[46:49], v51 offset:44032
	s_waitcnt lgkmcnt(0)
	v_fma_f32 v44, v54, v44, v48
	v_fma_f32 v45, v55, v45, v49
	v_fma_f32 v42, v52, v42, v46
	v_fma_f32 v43, v53, v43, v47
	v_mul_f32_e32 v46, v34, v50
	v_mul_f32_e32 v47, v35, v50
	v_cvt_pk_bf16_f32 v42, v42, v43
	v_cvt_pk_bf16_f32 v43, v44, v45
	global_store_dwordx2 v[26:27], v[42:43], off offset:1536
	v_mul_f32_e32 v48, v36, v50
	v_mul_f32_e32 v49, v37, v50
	ds_read_b128 v[34:37], v51 offset:4096
	ds_read_b128 v[42:45], v51 offset:45056
	s_waitcnt lgkmcnt(0)
	v_fma_f32 v36, v48, v36, v44
	v_fma_f32 v37, v49, v37, v45
	v_fma_f32 v34, v46, v34, v42
	v_fma_f32 v35, v47, v35, v43
	v_mul_f32_e32 v42, v38, v50
	v_mul_f32_e32 v43, v39, v50
	v_cvt_pk_bf16_f32 v34, v34, v35
	v_cvt_pk_bf16_f32 v35, v36, v37
	global_store_dwordx2 v[26:27], v[34:35], off offset:2048
	v_mul_f32_e32 v44, v40, v50
	v_mul_f32_e32 v45, v41, v50
	ds_read_b128 v[34:37], v51 offset:5120
	ds_read_b128 v[38:41], v51 offset:46080
	s_waitcnt lgkmcnt(0)
	v_fma_f32 v36, v44, v36, v40
	v_fma_f32 v37, v45, v37, v41
	v_fma_f32 v34, v42, v34, v38
	v_fma_f32 v35, v43, v35, v39
	s_waitcnt vmcnt(60)
	v_cvt_f32_f16_sdwa v43, v25 dst_sel:DWORD dst_unused:UNUSED_PAD src0_sel:WORD_1
	v_cvt_pk_bf16_f32 v34, v34, v35
	v_cvt_pk_bf16_f32 v35, v36, v37
	global_store_dwordx2 v[26:27], v[34:35], off offset:2560
	ds_read_b128 v[34:37], v51 offset:6144
	ds_read_b128 v[38:41], v51 offset:47104
	v_cvt_f32_f16_e32 v42, v25
	s_waitcnt lgkmcnt(0)
	v_fma_f32 v30, v30, v36, v40
	v_fma_f32 v31, v31, v37, v41
	v_fma_f32 v4, v4, v34, v38
	v_fma_f32 v5, v5, v35, v39
	v_mul_f32_e32 v36, v32, v50
	v_mul_f32_e32 v37, v33, v50
	v_cvt_pk_bf16_f32 v4, v4, v5
	v_cvt_pk_bf16_f32 v5, v30, v31
	global_store_dwordx2 v[26:27], v[4:5], off offset:3072
	v_mul_f32_e32 v4, v28, v50
	v_mul_f32_e32 v5, v29, v50
	ds_read_b128 v[28:31], v51 offset:7168
	ds_read_b128 v[32:35], v51 offset:48128
	v_cvt_f32_f16_sdwa v41, v24 dst_sel:DWORD dst_unused:UNUSED_PAD src0_sel:WORD_1
	v_cvt_f32_f16_e32 v40, v24
	s_waitcnt vmcnt(61)
	v_cvt_f32_f16_sdwa v39, v23 dst_sel:DWORD dst_unused:UNUSED_PAD src0_sel:WORD_1
	v_cvt_f32_f16_e32 v38, v23
	s_waitcnt lgkmcnt(0)
	v_fma_f32 v30, v36, v30, v34
	v_fma_f32 v31, v37, v31, v35
	v_cvt_f32_f16_sdwa v37, v22 dst_sel:DWORD dst_unused:UNUSED_PAD src0_sel:WORD_1
	v_cvt_f32_f16_e32 v36, v22
	v_fma_f32 v4, v4, v28, v32
	v_fma_f32 v5, v5, v29, v33
	v_mov_b32_e32 v22, v41
	v_cvt_pk_bf16_f32 v4, v4, v5
	v_cvt_pk_bf16_f32 v5, v30, v31
	global_store_dwordx2 v[26:27], v[4:5], off offset:3584
	v_mov_b32_e32 v23, v37
	s_waitcnt vmcnt(61)
	v_cvt_f32_f16_sdwa v27, v20 dst_sel:DWORD dst_unused:UNUSED_PAD src0_sel:WORD_1
	v_cvt_f32_f16_sdwa v29, v21 dst_sel:DWORD dst_unused:UNUSED_PAD src0_sel:WORD_1
	v_mov_b32_e32 v4, v40
	v_mov_b32_e32 v5, v36
	v_mul_f32_e32 v22, v22, v22
	v_mul_f32_e32 v23, v23, v23
	v_mov_b32_e32 v24, v43
	v_mov_b32_e32 v25, v39
	v_cvt_f32_f16_e32 v26, v20
	v_cvt_f32_f16_e32 v28, v21
	s_waitcnt vmcnt(60)
	v_cvt_f32_f16_sdwa v31, v18 dst_sel:DWORD dst_unused:UNUSED_PAD src0_sel:WORD_1
	v_fma_f32 v4, v4, v4, v22
	v_fma_f32 v5, v5, v5, v23
	v_mov_b32_e32 v22, v42
	v_mov_b32_e32 v23, v38
	v_mul_f32_e32 v24, v24, v24
	v_mul_f32_e32 v25, v25, v25
	v_cvt_f32_f16_e32 v30, v18
	v_cvt_f32_f16_sdwa v33, v19 dst_sel:DWORD dst_unused:UNUSED_PAD src0_sel:WORD_1
	v_fma_f32 v22, v22, v22, v24
	v_fma_f32 v23, v23, v23, v25
	v_cvt_f32_f16_e32 v32, v19
	v_add_f32_e32 v4, v4, v22
	v_add_f32_e32 v5, v5, v23
	v_mov_b32_e32 v22, v27
	v_mov_b32_e32 v23, v29
	v_mov_b32_e32 v20, v26
	v_mov_b32_e32 v21, v28
	v_mul_f32_e32 v22, v22, v22
	v_mul_f32_e32 v23, v23, v23
	v_mul_f32_e32 v18, v31, v31
	v_fma_f32 v20, v20, v20, v22
	v_fma_f32 v21, v21, v21, v23
	v_fma_f32 v24, v30, v30, v18
	v_fma_f32 v25, v31, v31, v18
	v_mul_f32_e32 v18, v33, v33
	v_add_f32_e32 v22, v20, v21
	v_add_f32_e32 v23, v21, v20
	v_fma_f32 v34, v32, v32, v18
	v_fma_f32 v35, v33, v33, v18
	s_waitcnt vmcnt(59)
	v_cvt_f32_f16_sdwa v19, v16 dst_sel:DWORD dst_unused:UNUSED_PAD src0_sel:WORD_1
	v_cvt_f32_f16_e32 v18, v16
	v_cvt_f32_f16_sdwa v21, v17 dst_sel:DWORD dst_unused:UNUSED_PAD src0_sel:WORD_1
	v_cvt_f32_f16_e32 v20, v17
	v_pk_add_f32 v[4:5], v[4:5], v[4:5] op_sel:[0,1] op_sel_hi:[1,0]
	v_mul_f32_e32 v16, v18, v18
	v_mul_f32_e32 v17, v19, v19
	v_mul_f32_e32 v44, v20, v20
	v_mul_f32_e32 v45, v21, v21
	v_mov_b32_e32 v5, v16
	v_mov_b32_e32 v23, v17
	v_mov_b32_e32 v25, v44
	v_mov_b32_e32 v35, v45
	v_add_f32_e32 v4, v4, v22
	v_add_f32_e32 v5, v5, v23
	v_add_f32_e32 v16, v24, v34
	v_add_f32_e32 v17, v25, v35
	s_waitcnt vmcnt(58)
; #define GAS __attribute__((address_space(1)))
; #define LAS __attribute__((address_space(3)))
; #define NR_LOAD(dst, k_) do { const GAS v2u* xr_ = (const GAS v2u*)(X + (size_t)(nw + 2048 * (k_)) * D) + F.lane; \
;         _Pragma("unroll") for (int j = 0; j < 8; ++j) dst[j] = __builtin_nontemporal_load(xr_ + 64 * j); } while (0)
; __device__ __forceinline__ void norm_mod_phase2(const Args& a, Frame& F, const float* gain, const float* modl, int sh_off, int sc_off, int nrows, const float* slab_gate) {
;     ...
;     NR_LOAD(r0, 0); NR_LOAD(r1, 1); NR_LOAD(r2, 2); NR_LOAD(r3, 3); NR_LOAD(r4, 4); NR_LOAD(r5, 5); NR_LOAD(r6, 6); NR_LOAD(r7, 7);
;     { const GAS f32x4* g4 = (const GAS f32x4*)gain;
;       for (int q = F.tid; q < 5 * D / 4; q += NWAVES * 64) { const int bq = q >> 9, cq = q & 511; const GAS f32x4* mb4 = (const GAS f32x4*)(modl + (size_t)bq * MOD_LD);
;           ((LAS f32x4*)CA)[q] = g4[cq] * (mb4[sc_off / 4 + cq] + 1.0f); ((LAS f32x4*)CB)[q] = mb4[sh_off / 4 + cq]; } }
;     asm volatile("s_waitcnt lgkmcnt(0)" ::: "memory"); __builtin_amdgcn_s_barrier(); asm volatile("" ::: "memory");
;     NR_FINISH(r0, nw,            (nw) >> 12);
;     NR_FINISH(r1, nw + 2048,     (nw + 2048) >> 12);
;     NR_FINISH(r2, nw + 2 * 2048, (nw + 2 * 2048) >> 12);
;     NR_FINISH(r3, nw + 3 * 2048, (nw + 3 * 2048) >> 12);
;     NR_FINISH(r4, nw + 4 * 2048, (nw + 4 * 2048) >> 12);
;     NR_FINISH(r5, nw + 5 * 2048, (nw + 5 * 2048) >> 12);
;     NR_FINISH(r6, nw + 6 * 2048, (nw + 6 * 2048) >> 12);
;     NR_FINISH(r7, nw + 7 * 2048, (nw + 7 * 2048) >> 12);
;     if (ML + nw < nrows) {
;         const int r = ML + nw, rc = nw;
	v_cvt_f32_f16_sdwa v23, v14 dst_sel:DWORD dst_unused:UNUSED_PAD src0_sel:WORD_1
	v_cvt_f32_f16_sdwa v25, v15 dst_sel:DWORD dst_unused:UNUSED_PAD src0_sel:WORD_1
	v_cvt_f32_f16_e32 v22, v14
	v_cvt_f32_f16_e32 v24, v15
	v_add_f32_e32 v4, v4, v16
	v_add_f32_e32 v5, v5, v17
	v_mov_b32_e32 v14, v23
	v_mov_b32_e32 v15, v25
	v_add_f32_e32 v34, v4, v5
	v_add_f32_e32 v35, v5, v4
	v_mov_b32_e32 v4, v22
	v_mov_b32_e32 v5, v24
	v_mul_f32_e32 v14, v14, v14
	v_mul_f32_e32 v15, v15, v15
	s_waitcnt vmcnt(56)
	v_cvt_f32_f16_sdwa v17, v11 dst_sel:DWORD dst_unused:UNUSED_PAD src0_sel:WORD_1
	v_fma_f32 v4, v4, v4, v14
	v_fma_f32 v5, v5, v5, v15
	v_cvt_f32_f16_sdwa v15, v13 dst_sel:DWORD dst_unused:UNUSED_PAD src0_sel:WORD_1
	v_add_f32_e32 v44, v4, v5
	v_add_f32_e32 v45, v5, v4
	v_cvt_f32_f16_sdwa v5, v12 dst_sel:DWORD dst_unused:UNUSED_PAD src0_sel:WORD_1
	v_cvt_f32_f16_e32 v4, v12
	v_cvt_f32_f16_e32 v14, v13
	v_cvt_f32_f16_e32 v16, v11
	v_mul_f32_e32 v12, v5, v5
	v_fma_f32 v46, v4, v4, v12
	v_fma_f32 v47, v5, v5, v12
	v_mul_f32_e32 v12, v15, v15
	v_fma_f32 v48, v14, v14, v12
	v_fma_f32 v49, v15, v15, v12
	v_cvt_f32_f16_sdwa v13, v10 dst_sel:DWORD dst_unused:UNUSED_PAD src0_sel:WORD_1
	v_cvt_f32_f16_e32 v12, v10
	v_mul_f32_e32 v50, v16, v16
	v_mul_f32_e32 v51, v17, v17
	v_mul_f32_e32 v10, v12, v12
	v_mul_f32_e32 v11, v13, v13
	s_nop 0
	v_mov_b32_e32 v35, v10
	v_mov_b32_e32 v45, v11
	v_mov_b32_e32 v47, v50
	v_mov_b32_e32 v49, v51
	v_add_f32_e32 v10, v34, v44
	v_add_f32_e32 v11, v35, v45
	v_add_f32_e32 v34, v46, v48
	v_add_f32_e32 v35, v47, v49
	s_nop 0
	v_add_f32_e32 v10, v10, v34
	v_add_f32_e32 v11, v11, v35
	s_nop 0
	v_add_f32_e32 v10, v10, v11
	s_nop 1
	v_add_f32_dpp v10, v10, v10 quad_perm:[1,0,3,2] row_mask:0xf bank_mask:0xf bound_ctrl:1
	s_nop 1
	v_add_f32_dpp v10, v10, v10 quad_perm:[2,3,0,1] row_mask:0xf bank_mask:0xf bound_ctrl:1
	s_nop 1
	v_add_f32_dpp v10, v10, v10 row_half_mirror row_mask:0xf bank_mask:0xf bound_ctrl:1
	s_nop 1
	v_add_f32_dpp v10, v10, v10 row_mirror row_mask:0xf bank_mask:0xf bound_ctrl:1
	s_nop 0
	v_readlane_b32 s8, v10, 16
	v_readlane_b32 s9, v10, 48
	v_readlane_b32 s6, v10, 0
	v_readlane_b32 s7, v10, 32
	v_mov_b32_e32 v10, s8
	v_mov_b32_e32 v11, s9
	v_add_f32_e32 v10, s6, v10
	v_add_f32_e32 v11, s7, v11
	s_nop 0
	v_add_f32_e32 v10, v10, v11
	v_fmamk_f32 v10, v10, 0x3a000000, v252
	v_cmp_gt_f32_e32 vcc, s55, v10
	v_mul_f32_e32 v11, 0x4f800000, v10
	s_nop 0
	v_cndmask_b32_e32 v10, v10, v11, vcc
	v_sqrt_f32_e32 v11, v10
	s_nop 0
	v_add_u32_e32 v34, -1, v11
	v_fma_f32 v35, -v34, v11, v10
	v_cmp_ge_f32_e64 s[8:9], 0, v35
	v_add_u32_e32 v35, 1, v11
	s_nop 0
	v_cndmask_b32_e64 v34, v11, v34, s[8:9]
	v_fma_f32 v11, -v35, v11, v10
	v_cmp_lt_f32_e64 s[8:9], 0, v11
	s_nop 1
	v_cndmask_b32_e64 v11, v34, v35, s[8:9]
	v_mul_f32_e32 v34, 0x37800000, v11
	v_cndmask_b32_e32 v11, v11, v34, vcc
	v_cmp_class_f32_e32 vcc, v10, v253
	s_add_i32 s8, s10, 0x4000
	s_nop 0
	v_cndmask_b32_e32 v10, v11, v10, vcc
	v_div_scale_f32 v11, s[6:7], v10, v10, 1.0
	v_rcp_f32_e32 v34, v11
	s_lshl_b32 s6, s14, 1
	s_and_b32 s6, s6, 0xffffe000
	s_add_i32 s6, s6, 0
	v_fma_f32 v35, -v11, v34, 1.0
	v_fmac_f32_e32 v34, v35, v34
	v_div_scale_f32 v35, vcc, 1.0, v10, 1.0
	v_mul_f32_e32 v44, v35, v34
	v_fma_f32 v45, -v11, v44, v35
	v_fmac_f32_e32 v44, v45, v34
	v_fma_f32 v11, -v11, v44, v35
	v_div_fmas_f32 v11, v11, v34, v44
	v_div_fixup_f32 v34, v11, v10, 1.0
	v_mul_f32_e32 v48, v40, v34
	v_mul_f32_e32 v49, v41, v34
	v_mul_f32_e32 v50, v42, v34
	v_mul_f32_e32 v51, v43, v34
	v_add_u32_e32 v35, s6, v0
	ds_read_b128 v[40:43], v35
	ds_read_b128 v[44:47], v35 offset:40960
	v_lshl_add_u64 v[10:11], s[16:17], 1, v[2:3]
	v_lshl_add_u64 v[10:11], v[10:11], 0, v[6:7]
	v_mul_f32_e32 v4, v4, v34
	v_mul_f32_e32 v5, v5, v34
	v_mul_f32_e32 v14, v14, v34
	v_mul_f32_e32 v15, v15, v34
	s_waitcnt lgkmcnt(0)
	v_fma_f32 v42, v42, v50, v46
	v_fma_f32 v43, v43, v51, v47
	v_fma_f32 v40, v40, v48, v44
	v_fma_f32 v41, v41, v49, v45
	v_mul_f32_e32 v44, v36, v34
	v_mul_f32_e32 v45, v37, v34
	v_cvt_pk_bf16_f32 v40, v40, v41
	v_cvt_pk_bf16_f32 v41, v42, v43
	global_store_dwordx2 v[10:11], v[40:41], off
	v_mul_f32_e32 v46, v38, v34
	v_mul_f32_e32 v47, v39, v34
	ds_read_b128 v[36:39], v35 offset:1024
	ds_read_b128 v[40:43], v35 offset:41984
	s_cmp_lt_i32 s8, s47
	s_waitcnt lgkmcnt(0)
	v_fma_f32 v38, v38, v46, v42
	v_fma_f32 v39, v39, v47, v43
	v_fma_f32 v36, v36, v44, v40
	v_fma_f32 v37, v37, v45, v41
	v_mul_f32_e32 v40, v26, v34
	v_mul_f32_e32 v41, v27, v34
	v_cvt_pk_bf16_f32 v36, v36, v37
	v_cvt_pk_bf16_f32 v37, v38, v39
	global_store_dwordx2 v[10:11], v[36:37], off offset:512
	v_mul_f32_e32 v42, v28, v34
	v_mul_f32_e32 v43, v29, v34
	ds_read_b128 v[26:29], v35 offset:2048
	ds_read_b128 v[36:39], v35 offset:43008
	s_waitcnt lgkmcnt(0)
	v_fma_f32 v28, v28, v42, v38
	v_fma_f32 v29, v29, v43, v39
	v_fma_f32 v26, v26, v40, v36
	v_fma_f32 v27, v27, v41, v37
	v_mul_f32_e32 v36, v30, v34
	v_mul_f32_e32 v37, v31, v34
	v_cvt_pk_bf16_f32 v26, v26, v27
	v_cvt_pk_bf16_f32 v27, v28, v29
	global_store_dwordx2 v[10:11], v[26:27], off offset:1024
	v_mul_f32_e32 v38, v32, v34
	v_mul_f32_e32 v39, v33, v34
	ds_read_b128 v[26:29], v35 offset:3072
	ds_read_b128 v[30:33], v35 offset:44032
	s_waitcnt lgkmcnt(0)
	v_fma_f32 v28, v38, v28, v32
	v_fma_f32 v29, v39, v29, v33
	v_fma_f32 v26, v36, v26, v30
	v_fma_f32 v27, v37, v27, v31
	v_mul_f32_e32 v30, v18, v34
	v_mul_f32_e32 v31, v19, v34
	v_cvt_pk_bf16_f32 v26, v26, v27
	v_cvt_pk_bf16_f32 v27, v28, v29
	global_store_dwordx2 v[10:11], v[26:27], off offset:1536
	v_mul_f32_e32 v32, v20, v34
	v_mul_f32_e32 v33, v21, v34
	ds_read_b128 v[18:21], v35 offset:4096
	ds_read_b128 v[26:29], v35 offset:45056
	s_waitcnt lgkmcnt(0)
; #define GAS __attribute__((address_space(1)))
; __device__ __forceinline__ unsigned xpk2(float lo, float hi) { if (XRES_F16) { const f32x2_t v = {lo, hi}; const f16x2_t h = __builtin_convertvector(v, f16x2_t); return __builtin_bit_cast(unsigned, h); } return pk2(lo, hi); }
; __device__ __forceinline__ float xlo(unsigned w) { if (XRES_F16) { const f16x2_t h = __builtin_bit_cast(f16x2_t, w); return (float)h[0]; } return __builtin_bit_cast(float, w << 16); }
; __device__ __forceinline__ float xhi(unsigned w) { if (XRES_F16) { const f16x2_t h = __builtin_bit_cast(f16x2_t, w); return (float)h[1]; } return __builtin_bit_cast(float, w & 0xffff0000u); }
; __device__ __forceinline__ void norm_mod_phase2(const Args& a, Frame& F, const float* gain, const float* modl, int sh_off, int sc_off, int nrows, const float* slab_gate) {
;     ...
;     if (ML + nw < nrows) {
;         const int r = ML + nw, rc = nw;
;         const GAS v2u* xr = (const GAS v2u*)(X + (size_t)r * D) + F.lane;
; #pragma unroll
;         for (int j = 0; j < 8; ++j) r0[j] = xr[64 * j];
;         if (slab_gate != nullptr) { const GAS f32x4* sl = (const GAS f32x4*)((const float*)(a.ws + WS_SLAB) + (size_t)rc * D) + F.lane;
; #pragma unroll
;             for (int j = 0; j < 8; ++j) { const f32x4 p = (sl[64 * j] + sl[64 * j + (size_t)MC * D / 4]) + (sl[64 * j + 2 * ((size_t)MC * D / 4)] + sl[64 * j + 3 * ((size_t)MC * D / 4)]);
;                 const f32x4 x = (f32x4){xlo(r0[j].x), xhi(r0[j].x), xlo(r0[j].y), xhi(r0[j].y)} + *(const GAS f32x4*)(slab_gate + 256 * j + 4 * F.lane) * p;
;                 v2u w; w.x = xpk2(x[0], x[1]); w.y = xpk2(x[2], x[3]); ((GAS v2u*)(X + (size_t)r * D) + F.lane)[64 * j] = w; r0[j] = w; } }
	v_fma_f32 v20, v32, v20, v28
	v_fma_f32 v21, v33, v21, v29
	v_fma_f32 v18, v30, v18, v26
	v_fma_f32 v19, v31, v19, v27
	v_mul_f32_e32 v26, v22, v34
	v_mul_f32_e32 v27, v23, v34
	v_cvt_pk_bf16_f32 v18, v18, v19
	v_cvt_pk_bf16_f32 v19, v20, v21
	global_store_dwordx2 v[10:11], v[18:19], off offset:2048
	v_mul_f32_e32 v28, v24, v34
	v_mul_f32_e32 v29, v25, v34
	ds_read_b128 v[18:21], v35 offset:5120
	ds_read_b128 v[22:25], v35 offset:46080
	s_waitcnt lgkmcnt(0)
	v_fma_f32 v20, v28, v20, v24
	v_fma_f32 v21, v29, v21, v25
	v_fma_f32 v18, v26, v18, v22
	v_fma_f32 v19, v27, v19, v23
	s_nop 0
	v_cvt_pk_bf16_f32 v18, v18, v19
	v_cvt_pk_bf16_f32 v19, v20, v21
	global_store_dwordx2 v[10:11], v[18:19], off offset:2560
	ds_read_b128 v[18:21], v35 offset:6144
	ds_read_b128 v[22:25], v35 offset:47104
	s_waitcnt lgkmcnt(0)
	v_fma_f32 v14, v14, v20, v24
	v_fma_f32 v15, v15, v21, v25
	v_fma_f32 v4, v4, v18, v22
	v_fma_f32 v5, v5, v19, v23
	v_mul_f32_e32 v20, v16, v34
	v_mul_f32_e32 v21, v17, v34
	v_cvt_pk_bf16_f32 v4, v4, v5
	v_cvt_pk_bf16_f32 v5, v14, v15
	global_store_dwordx2 v[10:11], v[4:5], off offset:3072
	v_mul_f32_e32 v4, v12, v34
	v_mul_f32_e32 v5, v13, v34
	ds_read_b128 v[12:15], v35 offset:7168
	ds_read_b128 v[16:19], v35 offset:48128
	s_waitcnt lgkmcnt(0)
	v_fma_f32 v14, v20, v14, v18
	v_fma_f32 v15, v21, v15, v19
	v_fma_f32 v4, v4, v12, v16
	v_fma_f32 v5, v5, v13, v17
	s_nop 0
	v_cvt_pk_bf16_f32 v4, v4, v5
	v_cvt_pk_bf16_f32 v5, v14, v15
	global_store_dwordx2 v[10:11], v[4:5], off offset:3584
	s_cbranch_scc0 .LBB0_1050
	s_ashr_i32 s9, s8, 31
	s_lshl_b64 s[6:7], s[8:9], 12
	v_lshl_add_u64 v[4:5], v[8:9], 0, s[6:7]
	v_lshl_add_u64 v[18:19], v[4:5], 0, v[6:7]
	global_load_dwordx2 v[22:23], v[18:19], off
	global_load_dwordx2 v[20:21], v[18:19], off offset:512
	global_load_dwordx2 v[16:17], v[18:19], off offset:1024
	global_load_dwordx2 v[12:13], v[18:19], off offset:1536
	global_load_dwordx2 v[14:15], v[18:19], off offset:2048
	global_load_dwordx2 v[10:11], v[18:19], off offset:2560
	global_load_dwordx2 v[8:9], v[18:19], off offset:3072
	global_load_dwordx2 v[4:5], v[18:19], off offset:3584
	s_andn2_b64 vcc, exec, s[4:5]
	v_lshlrev_b32_e32 v46, 2, v147
	s_cbranch_vccnz .LBB0_1049
	v_mov_b32_e32 v24, s72
	v_mov_b32_e32 v25, s73
	v_lshl_add_u64 v[24:25], s[12:13], 2, v[24:25]
	v_lshl_add_u64 v[24:25], v[24:25], 0, v[0:1]
	v_lshlrev_b32_e32 v0, 2, v46
	v_lshl_add_u64 v[26:27], s[86:87], 0, v[0:1]
	v_add_co_u32_e32 v28, vcc, 0x58400000, v24
	s_nop 1
	v_addc_co_u32_e32 v29, vcc, 0, v25, vcc
	v_add_co_u32_e32 v30, vcc, 0x58c00000, v24
	s_nop 1
	v_addc_co_u32_e32 v31, vcc, 0, v25, vcc
	v_add_co_u32_e32 v32, vcc, 0x59400000, v24
	s_nop 1
	v_addc_co_u32_e32 v33, vcc, 0, v25, vcc
	v_add_co_u32_e32 v34, vcc, 0x59c00000, v24
	s_nop 1
	v_addc_co_u32_e32 v35, vcc, 0, v25, vcc
	v_add_co_u32_e32 v36, vcc, 0x58401000, v24
	s_nop 1
	v_addc_co_u32_e32 v37, vcc, 0, v25, vcc
	v_add_co_u32_e32 v38, vcc, 0x58c01000, v24
	s_nop 1
	v_addc_co_u32_e32 v39, vcc, 0, v25, vcc
	v_add_co_u32_e32 v42, vcc, 0x59401000, v24
	s_nop 1
	v_addc_co_u32_e32 v43, vcc, 0, v25, vcc
	v_add_co_u32_e32 v44, vcc, 0x59c01000, v24
	s_nop 1
	v_addc_co_u32_e32 v45, vcc, 0, v25, vcc
	v_add_co_u32_e32 v48, vcc, 0x34000, v26
	s_nop 1
	v_addc_co_u32_e32 v49, vcc, 0, v27, vcc
	v_add_co_u32_e32 v50, vcc, 0x35000, v26
	s_nop 1
	v_addc_co_u32_e32 v51, vcc, 0, v27, vcc
	global_load_dwordx4 v[94:97], v[28:29], off
	global_load_dwordx4 v[98:101], v[30:31], off
	global_load_dwordx4 v[102:105], v[32:33], off
	global_load_dwordx4 v[106:109], v[34:35], off
	global_load_dwordx4 v[110:113], v[48:49], off
	global_load_dwordx4 v[114:117], v[28:29], off offset:1024
	global_load_dwordx4 v[118:121], v[30:31], off offset:1024
	global_load_dwordx4 v[122:125], v[32:33], off offset:1024
	global_load_dwordx4 v[126:129], v[34:35], off offset:1024
	global_load_dwordx4 v[130:133], v[48:49], off offset:1024
	global_load_dwordx4 v[134:137], v[28:29], off offset:2048
	global_load_dwordx4 v[138:141], v[30:31], off offset:2048
	global_load_dwordx4 v[142:145], v[32:33], off offset:2048
	global_load_dwordx4 v[146:149], v[34:35], off offset:2048
	global_load_dwordx4 v[150:153], v[48:49], off offset:2048
	global_load_dwordx4 v[154:157], v[28:29], off offset:3072
	global_load_dwordx4 v[158:161], v[30:31], off offset:3072
	global_load_dwordx4 v[162:165], v[32:33], off offset:3072
	global_load_dwordx4 v[170:173], v[34:35], off offset:3072
	global_load_dwordx4 v[174:177], v[48:49], off offset:3072
	s_waitcnt vmcnt(15)
	v_add_f32_e32 v220, v94, v98
	v_add_f32_e32 v221, v95, v99
	v_add_f32_e32 v222, v96, v100
	v_add_f32_e32 v223, v97, v101
	v_add_f32_e32 v224, v102, v106
	v_add_f32_e32 v225, v103, v107
	v_add_f32_e32 v226, v104, v108
	v_add_f32_e32 v227, v105, v109
	v_cvt_f32_f16_e32 v232, v22
	v_cvt_f32_f16_sdwa v233, v22 dst_sel:DWORD dst_unused:UNUSED_PAD src0_sel:WORD_1
	v_cvt_f32_f16_e32 v234, v23
	v_cvt_f32_f16_sdwa v235, v23 dst_sel:DWORD dst_unused:UNUSED_PAD src0_sel:WORD_1
	v_add_f32_e32 v228, v220, v224
	v_add_f32_e32 v229, v221, v225
	v_add_f32_e32 v230, v222, v226
	v_add_f32_e32 v231, v223, v227
	s_nop 1
	v_fma_f32 v236, v110, v228, v232
	v_fma_f32 v237, v111, v229, v233
	v_fma_f32 v238, v112, v230, v234
	v_fma_f32 v239, v113, v231, v235
	s_nop 1
	v_cvt_pk_f16_f32 v22, v236, v237
	v_cvt_pk_f16_f32 v23, v238, v239
	global_store_dwordx2 v[18:19], v[22:23], off
	global_load_dwordx4 v[94:97], v[36:37], off
	global_load_dwordx4 v[98:101], v[38:39], off
	global_load_dwordx4 v[102:105], v[42:43], off
	global_load_dwordx4 v[106:109], v[44:45], off
	global_load_dwordx4 v[110:113], v[50:51], off
	s_waitcnt vmcnt(16)
; #define GAS __attribute__((address_space(1)))
; __device__ __forceinline__ unsigned xpk2(float lo, float hi) { if (XRES_F16) { const f32x2_t v = {lo, hi}; const f16x2_t h = __builtin_convertvector(v, f16x2_t); return __builtin_bit_cast(unsigned, h); } return pk2(lo, hi); }
; __device__ __forceinline__ float xlo(unsigned w) { if (XRES_F16) { const f16x2_t h = __builtin_bit_cast(f16x2_t, w); return (float)h[0]; } return __builtin_bit_cast(float, w << 16); }
; __device__ __forceinline__ float xhi(unsigned w) { if (XRES_F16) { const f16x2_t h = __builtin_bit_cast(f16x2_t, w); return (float)h[1]; } return __builtin_bit_cast(float, w & 0xffff0000u); }
; __device__ __forceinline__ void norm_mod_phase2(const Args& a, Frame& F, const float* gain, const float* modl, int sh_off, int sc_off, int nrows, const float* slab_gate) {
;     ...
;             for (int j = 0; j < 8; ++j) { const f32x4 p = (sl[64 * j] + sl[64 * j + (size_t)MC * D / 4]) + (sl[64 * j + 2 * ((size_t)MC * D / 4)] + sl[64 * j + 3 * ((size_t)MC * D / 4)]);
;                 const f32x4 x = (f32x4){xlo(r0[j].x), xhi(r0[j].x), xlo(r0[j].y), xhi(r0[j].y)} + *(const GAS f32x4*)(slab_gate + 256 * j + 4 * F.lane) * p;
;                 v2u w; w.x = xpk2(x[0], x[1]); w.y = xpk2(x[2], x[3]); ((GAS v2u*)(X + (size_t)r * D) + F.lane)[64 * j] = w; r0[j] = w; } }
	v_add_f32_e32 v220, v114, v118
	v_add_f32_e32 v221, v115, v119
	v_add_f32_e32 v222, v116, v120
	v_add_f32_e32 v223, v117, v121
	v_add_f32_e32 v224, v122, v126
	v_add_f32_e32 v225, v123, v127
	v_add_f32_e32 v226, v124, v128
	v_add_f32_e32 v227, v125, v129
	v_cvt_f32_f16_e32 v232, v20
	v_cvt_f32_f16_sdwa v233, v20 dst_sel:DWORD dst_unused:UNUSED_PAD src0_sel:WORD_1
	v_cvt_f32_f16_e32 v234, v21
	v_cvt_f32_f16_sdwa v235, v21 dst_sel:DWORD dst_unused:UNUSED_PAD src0_sel:WORD_1
	v_add_f32_e32 v228, v220, v224
	v_add_f32_e32 v229, v221, v225
	v_add_f32_e32 v230, v222, v226
	v_add_f32_e32 v231, v223, v227
	s_nop 1
	v_fma_f32 v236, v130, v228, v232
	v_fma_f32 v237, v131, v229, v233
	v_fma_f32 v238, v132, v230, v234
	v_fma_f32 v239, v133, v231, v235
	s_nop 1
	v_cvt_pk_f16_f32 v20, v236, v237
	v_cvt_pk_f16_f32 v21, v238, v239
	global_store_dwordx2 v[18:19], v[20:21], off offset:512
	global_load_dwordx4 v[114:117], v[36:37], off offset:1024
	global_load_dwordx4 v[118:121], v[38:39], off offset:1024
	global_load_dwordx4 v[122:125], v[42:43], off offset:1024
	global_load_dwordx4 v[126:129], v[44:45], off offset:1024
	global_load_dwordx4 v[130:133], v[50:51], off offset:1024
	s_waitcnt vmcnt(17)
	v_add_f32_e32 v220, v134, v138
	v_add_f32_e32 v221, v135, v139
	v_add_f32_e32 v222, v136, v140
	v_add_f32_e32 v223, v137, v141
	v_add_f32_e32 v224, v142, v146
	v_add_f32_e32 v225, v143, v147
	v_add_f32_e32 v226, v144, v148
	v_add_f32_e32 v227, v145, v149
	v_cvt_f32_f16_e32 v232, v16
	v_cvt_f32_f16_sdwa v233, v16 dst_sel:DWORD dst_unused:UNUSED_PAD src0_sel:WORD_1
	v_cvt_f32_f16_e32 v234, v17
	v_cvt_f32_f16_sdwa v235, v17 dst_sel:DWORD dst_unused:UNUSED_PAD src0_sel:WORD_1
	v_add_f32_e32 v228, v220, v224
	v_add_f32_e32 v229, v221, v225
	v_add_f32_e32 v230, v222, v226
	v_add_f32_e32 v231, v223, v227
	s_nop 1
	v_fma_f32 v236, v150, v228, v232
	v_fma_f32 v237, v151, v229, v233
	v_fma_f32 v238, v152, v230, v234
	v_fma_f32 v239, v153, v231, v235
	s_nop 1
	v_cvt_pk_f16_f32 v16, v236, v237
	v_cvt_pk_f16_f32 v17, v238, v239
	global_store_dwordx2 v[18:19], v[16:17], off offset:1024
	global_load_dwordx4 v[134:137], v[36:37], off offset:2048
	global_load_dwordx4 v[138:141], v[38:39], off offset:2048
	global_load_dwordx4 v[142:145], v[42:43], off offset:2048
	global_load_dwordx4 v[146:149], v[44:45], off offset:2048
	global_load_dwordx4 v[150:153], v[50:51], off offset:2048
	s_waitcnt vmcnt(18)
	v_add_f32_e32 v220, v154, v158
	v_add_f32_e32 v221, v155, v159
	v_add_f32_e32 v222, v156, v160
	v_add_f32_e32 v223, v157, v161
	v_add_f32_e32 v224, v162, v170
	v_add_f32_e32 v225, v163, v171
	v_add_f32_e32 v226, v164, v172
	v_add_f32_e32 v227, v165, v173
	v_cvt_f32_f16_e32 v232, v12
	v_cvt_f32_f16_sdwa v233, v12 dst_sel:DWORD dst_unused:UNUSED_PAD src0_sel:WORD_1
	v_cvt_f32_f16_e32 v234, v13
	v_cvt_f32_f16_sdwa v235, v13 dst_sel:DWORD dst_unused:UNUSED_PAD src0_sel:WORD_1
	v_add_f32_e32 v228, v220, v224
	v_add_f32_e32 v229, v221, v225
	v_add_f32_e32 v230, v222, v226
	v_add_f32_e32 v231, v223, v227
	s_nop 1
	v_fma_f32 v236, v174, v228, v232
	v_fma_f32 v237, v175, v229, v233
	v_fma_f32 v238, v176, v230, v234
	v_fma_f32 v239, v177, v231, v235
	s_nop 1
	v_cvt_pk_f16_f32 v12, v236, v237
	v_cvt_pk_f16_f32 v13, v238, v239
	global_store_dwordx2 v[18:19], v[12:13], off offset:1536
	global_load_dwordx4 v[154:157], v[36:37], off offset:3072
	global_load_dwordx4 v[158:161], v[38:39], off offset:3072
	global_load_dwordx4 v[162:165], v[42:43], off offset:3072
	global_load_dwordx4 v[170:173], v[44:45], off offset:3072
	global_load_dwordx4 v[174:177], v[50:51], off offset:3072
	s_waitcnt vmcnt(18)
	v_add_f32_e32 v220, v94, v98
	v_add_f32_e32 v221, v95, v99
	v_add_f32_e32 v222, v96, v100
	v_add_f32_e32 v223, v97, v101
	v_add_f32_e32 v224, v102, v106
	v_add_f32_e32 v225, v103, v107
	v_add_f32_e32 v226, v104, v108
	v_add_f32_e32 v227, v105, v109
	v_cvt_f32_f16_e32 v232, v14
	v_cvt_f32_f16_sdwa v233, v14 dst_sel:DWORD dst_unused:UNUSED_PAD src0_sel:WORD_1
	v_cvt_f32_f16_e32 v234, v15
	v_cvt_f32_f16_sdwa v235, v15 dst_sel:DWORD dst_unused:UNUSED_PAD src0_sel:WORD_1
	v_add_f32_e32 v228, v220, v224
	v_add_f32_e32 v229, v221, v225
	v_add_f32_e32 v230, v222, v226
	v_add_f32_e32 v231, v223, v227
	s_nop 1
	v_fma_f32 v236, v110, v228, v232
	v_fma_f32 v237, v111, v229, v233
	v_fma_f32 v238, v112, v230, v234
	v_fma_f32 v239, v113, v231, v235
	s_nop 1
	v_cvt_pk_f16_f32 v14, v236, v237
	v_cvt_pk_f16_f32 v15, v238, v239
	global_store_dwordx2 v[18:19], v[14:15], off offset:2048
	s_waitcnt vmcnt(13)
	v_add_f32_e32 v220, v114, v118
	v_add_f32_e32 v221, v115, v119
	v_add_f32_e32 v222, v116, v120
	v_add_f32_e32 v223, v117, v121
	v_add_f32_e32 v224, v122, v126
	v_add_f32_e32 v225, v123, v127
	v_add_f32_e32 v226, v124, v128
	v_add_f32_e32 v227, v125, v129
	v_cvt_f32_f16_e32 v232, v10
	v_cvt_f32_f16_sdwa v233, v10 dst_sel:DWORD dst_unused:UNUSED_PAD src0_sel:WORD_1
	v_cvt_f32_f16_e32 v234, v11
	v_cvt_f32_f16_sdwa v235, v11 dst_sel:DWORD dst_unused:UNUSED_PAD src0_sel:WORD_1
	v_add_f32_e32 v228, v220, v224
	v_add_f32_e32 v229, v221, v225
	v_add_f32_e32 v230, v222, v226
	v_add_f32_e32 v231, v223, v227
	s_nop 1
	v_fma_f32 v236, v130, v228, v232
	v_fma_f32 v237, v131, v229, v233
	v_fma_f32 v238, v132, v230, v234
	v_fma_f32 v239, v133, v231, v235
	s_nop 1
	v_cvt_pk_f16_f32 v10, v236, v237
	v_cvt_pk_f16_f32 v11, v238, v239
	global_store_dwordx2 v[18:19], v[10:11], off offset:2560
	s_waitcnt vmcnt(8)
; #define GAS __attribute__((address_space(1)))
; __device__ __forceinline__ unsigned xpk2(float lo, float hi) { if (XRES_F16) { const f32x2_t v = {lo, hi}; const f16x2_t h = __builtin_convertvector(v, f16x2_t); return __builtin_bit_cast(unsigned, h); } return pk2(lo, hi); }
; __device__ __forceinline__ float xlo(unsigned w) { if (XRES_F16) { const f16x2_t h = __builtin_bit_cast(f16x2_t, w); return (float)h[0]; } return __builtin_bit_cast(float, w << 16); }
; __device__ __forceinline__ float xhi(unsigned w) { if (XRES_F16) { const f16x2_t h = __builtin_bit_cast(f16x2_t, w); return (float)h[1]; } return __builtin_bit_cast(float, w & 0xffff0000u); }
; __device__ __forceinline__ void norm_mod_phase2(const Args& a, Frame& F, const float* gain, const float* modl, int sh_off, int sc_off, int nrows, const float* slab_gate) {
;     ...
;             for (int j = 0; j < 8; ++j) { const f32x4 p = (sl[64 * j] + sl[64 * j + (size_t)MC * D / 4]) + (sl[64 * j + 2 * ((size_t)MC * D / 4)] + sl[64 * j + 3 * ((size_t)MC * D / 4)]);
;                 const f32x4 x = (f32x4){xlo(r0[j].x), xhi(r0[j].x), xlo(r0[j].y), xhi(r0[j].y)} + *(const GAS f32x4*)(slab_gate + 256 * j + 4 * F.lane) * p;
;                 v2u w; w.x = xpk2(x[0], x[1]); w.y = xpk2(x[2], x[3]); ((GAS v2u*)(X + (size_t)r * D) + F.lane)[64 * j] = w; r0[j] = w; } }
;         NR_FINISH(r0, r, 4);
	v_add_f32_e32 v220, v134, v138
	v_add_f32_e32 v221, v135, v139
	v_add_f32_e32 v222, v136, v140
	v_add_f32_e32 v223, v137, v141
	v_add_f32_e32 v224, v142, v146
	v_add_f32_e32 v225, v143, v147
	v_add_f32_e32 v226, v144, v148
	v_add_f32_e32 v227, v145, v149
	v_cvt_f32_f16_e32 v232, v8
	v_cvt_f32_f16_sdwa v233, v8 dst_sel:DWORD dst_unused:UNUSED_PAD src0_sel:WORD_1
	v_cvt_f32_f16_e32 v234, v9
	v_cvt_f32_f16_sdwa v235, v9 dst_sel:DWORD dst_unused:UNUSED_PAD src0_sel:WORD_1
	v_add_f32_e32 v228, v220, v224
	v_add_f32_e32 v229, v221, v225
	v_add_f32_e32 v230, v222, v226
	v_add_f32_e32 v231, v223, v227
	s_nop 1
	v_fma_f32 v236, v150, v228, v232
	v_fma_f32 v237, v151, v229, v233
	v_fma_f32 v238, v152, v230, v234
	v_fma_f32 v239, v153, v231, v235
	s_nop 1
	v_cvt_pk_f16_f32 v8, v236, v237
	v_cvt_pk_f16_f32 v9, v238, v239
	global_store_dwordx2 v[18:19], v[8:9], off offset:3072
	s_waitcnt vmcnt(3)
	v_add_f32_e32 v220, v154, v158
	v_add_f32_e32 v221, v155, v159
	v_add_f32_e32 v222, v156, v160
	v_add_f32_e32 v223, v157, v161
	v_add_f32_e32 v224, v162, v170
	v_add_f32_e32 v225, v163, v171
	v_add_f32_e32 v226, v164, v172
	v_add_f32_e32 v227, v165, v173
	v_cvt_f32_f16_e32 v232, v4
	v_cvt_f32_f16_sdwa v233, v4 dst_sel:DWORD dst_unused:UNUSED_PAD src0_sel:WORD_1
	v_cvt_f32_f16_e32 v234, v5
	v_cvt_f32_f16_sdwa v235, v5 dst_sel:DWORD dst_unused:UNUSED_PAD src0_sel:WORD_1
	v_add_f32_e32 v228, v220, v224
	v_add_f32_e32 v229, v221, v225
	v_add_f32_e32 v230, v222, v226
	v_add_f32_e32 v231, v223, v227
	s_nop 1
	v_fma_f32 v236, v174, v228, v232
	v_fma_f32 v237, v175, v229, v233
	v_fma_f32 v238, v176, v230, v234
	v_fma_f32 v239, v177, v231, v235
	s_nop 1
	v_cvt_pk_f16_f32 v4, v236, v237
	v_cvt_pk_f16_f32 v5, v238, v239
	global_store_dwordx2 v[18:19], v[4:5], off offset:3584
.LBB0_1049:
	s_waitcnt vmcnt(7)
	v_cvt_f32_f16_sdwa v37, v22 dst_sel:DWORD dst_unused:UNUSED_PAD src0_sel:WORD_1
	s_waitcnt vmcnt(6)
	v_cvt_f32_f16_sdwa v33, v20 dst_sel:DWORD dst_unused:UNUSED_PAD src0_sel:WORD_1
	v_cvt_f32_f16_e32 v36, v22
	v_cvt_f32_f16_sdwa v39, v23 dst_sel:DWORD dst_unused:UNUSED_PAD src0_sel:WORD_1
	v_cvt_f32_f16_e32 v32, v20
	v_cvt_f32_f16_sdwa v35, v21 dst_sel:DWORD dst_unused:UNUSED_PAD src0_sel:WORD_1
	v_cvt_f32_f16_e32 v38, v23
	v_cvt_f32_f16_e32 v34, v21
	v_mov_b32_e32 v20, v37
	v_mov_b32_e32 v21, v33
	v_mov_b32_e32 v18, v36
	v_mov_b32_e32 v19, v32
	v_mul_f32_e32 v20, v20, v20
	v_mul_f32_e32 v21, v21, v21
	v_mov_b32_e32 v22, v39
	v_mov_b32_e32 v23, v35
	s_waitcnt vmcnt(5)
	v_cvt_f32_f16_sdwa v25, v16 dst_sel:DWORD dst_unused:UNUSED_PAD src0_sel:WORD_1
	v_cvt_f32_f16_sdwa v27, v17 dst_sel:DWORD dst_unused:UNUSED_PAD src0_sel:WORD_1
	v_fma_f32 v18, v18, v18, v20
	v_fma_f32 v19, v19, v19, v21
	v_mov_b32_e32 v20, v38
	v_mov_b32_e32 v21, v34
	v_mul_f32_e32 v22, v22, v22
	v_mul_f32_e32 v23, v23, v23
	v_cvt_f32_f16_e32 v24, v16
	v_cvt_f32_f16_e32 v26, v17
	v_fma_f32 v20, v20, v20, v22
	v_fma_f32 v21, v21, v21, v23
	s_waitcnt vmcnt(4)
	v_cvt_f32_f16_e32 v28, v12
	v_add_f32_e32 v18, v18, v20
	v_add_f32_e32 v19, v19, v21
	v_mov_b32_e32 v16, v24
	v_add_f32_e32 v20, v18, v18
	v_add_f32_e32 v21, v18, v19
	v_mov_b32_e32 v18, v25
	v_mov_b32_e32 v19, v27
	v_mov_b32_e32 v17, v26
	v_mul_f32_e32 v18, v18, v18
	v_mul_f32_e32 v19, v19, v19
	v_cvt_f32_f16_sdwa v29, v12 dst_sel:DWORD dst_unused:UNUSED_PAD src0_sel:WORD_1
	v_fma_f32 v16, v16, v16, v18
	v_fma_f32 v17, v17, v17, v19
	v_cvt_f32_f16_e32 v30, v13
	s_waitcnt vmcnt(3)
	v_cvt_f32_f16_sdwa v19, v15 dst_sel:DWORD dst_unused:UNUSED_PAD src0_sel:WORD_1
	v_cvt_f32_f16_e32 v18, v15
	v_add_f32_e32 v22, v16, v16
	v_add_f32_e32 v23, v16, v17
	v_cvt_f32_f16_sdwa v31, v13 dst_sel:DWORD dst_unused:UNUSED_PAD src0_sel:WORD_1
	v_cvt_f32_f16_sdwa v17, v14 dst_sel:DWORD dst_unused:UNUSED_PAD src0_sel:WORD_1
	v_cvt_f32_f16_e32 v16, v14
	v_mul_f32_e32 v0, v28, v28
	v_fma_f32 v12, v28, v28, v0
	v_fma_f32 v13, v29, v29, v0
	v_mul_f32_e32 v0, v30, v30
	v_mul_f32_e32 v42, v18, v18
	v_mul_f32_e32 v43, v19, v19
	v_fma_f32 v40, v30, v30, v0
	v_fma_f32 v41, v31, v31, v0
	v_mul_f32_e32 v14, v16, v16
	v_mul_f32_e32 v15, v17, v17
	v_mov_b32_e32 v22, v42
	v_mov_b32_e32 v20, v43
	v_mov_b32_e32 v12, v14
	v_mov_b32_e32 v40, v15
	v_add_f32_e32 v14, v22, v20
	v_add_f32_e32 v15, v23, v21
	s_waitcnt vmcnt(2)
	v_cvt_f32_f16_sdwa v21, v10 dst_sel:DWORD dst_unused:UNUSED_PAD src0_sel:WORD_1
	v_cvt_f32_f16_sdwa v23, v11 dst_sel:DWORD dst_unused:UNUSED_PAD src0_sel:WORD_1
	v_cvt_f32_f16_e32 v20, v10
	v_cvt_f32_f16_e32 v22, v11
	v_add_f32_e32 v12, v12, v40
	v_add_f32_e32 v13, v13, v41
	s_lshl_b64 s[10:11], s[8:9], 11
	v_add_f32_e32 v12, v12, v14
	v_add_f32_e32 v13, v13, v15
	v_mov_b32_e32 v10, v20
	v_add_f32_e32 v40, v12, v12
	v_add_f32_e32 v41, v12, v13
	v_mov_b32_e32 v12, v21
	v_mov_b32_e32 v13, v23
	v_mov_b32_e32 v11, v22
	v_mul_f32_e32 v12, v12, v12
	v_mul_f32_e32 v13, v13, v13
	s_waitcnt vmcnt(0)
; template <int CTRL> __device__ __forceinline__ float dpp_mov(float v) { return __builtin_bit_cast(float, __builtin_amdgcn_update_dpp(0, __builtin_bit_cast(int, v), CTRL, 0xF, 0xF, true)); }
; __device__ __forceinline__ float wave_sum(float v) {
;     v += dpp_mov<0xB1>(v);
;     v += dpp_mov<0x4E>(v);
;     v += dpp_mov<0x141>(v);
;     v += dpp_mov<0x140>(v);
;     const int iv = __builtin_bit_cast(int, v);
;     const float a = __builtin_bit_cast(float, __builtin_amdgcn_readlane(iv, 0)), b = __builtin_bit_cast(float, __builtin_amdgcn_readlane(iv, 16));
;     const float c = __builtin_bit_cast(float, __builtin_amdgcn_readlane(iv, 32)), d = __builtin_bit_cast(float, __builtin_amdgcn_readlane(iv, 48));
;     return (a + b) + (c + d);
; }
	v_cvt_f32_f16_sdwa v15, v5 dst_sel:DWORD dst_unused:UNUSED_PAD src0_sel:WORD_1
	v_fma_f32 v10, v10, v10, v12
	v_fma_f32 v11, v11, v11, v13
	v_cvt_f32_f16_e32 v12, v9
	v_add_f32_e32 v42, v10, v10
	v_add_f32_e32 v43, v10, v11
	v_cvt_f32_f16_e32 v10, v8
	v_cvt_f32_f16_sdwa v11, v8 dst_sel:DWORD dst_unused:UNUSED_PAD src0_sel:WORD_1
	v_cvt_f32_f16_sdwa v13, v9 dst_sel:DWORD dst_unused:UNUSED_PAD src0_sel:WORD_1
	v_cvt_f32_f16_sdwa v9, v4 dst_sel:DWORD dst_unused:UNUSED_PAD src0_sel:WORD_1
	v_cvt_f32_f16_e32 v8, v4
	v_cvt_f32_f16_e32 v14, v5
	v_mul_f32_e32 v0, v10, v10
	v_fma_f32 v44, v10, v10, v0
	v_fma_f32 v45, v11, v11, v0
	v_mul_f32_e32 v0, v12, v12
	v_fma_f32 v48, v12, v12, v0
	v_fma_f32 v49, v13, v13, v0
	v_mul_f32_e32 v4, v8, v8
	v_mul_f32_e32 v5, v9, v9
	v_mul_f32_e32 v50, v14, v14
	v_mul_f32_e32 v51, v15, v15
	v_mov_b32_e32 v44, v4
	v_mov_b32_e32 v48, v5
	v_mov_b32_e32 v42, v50
	v_mov_b32_e32 v40, v51
	v_add_f32_e32 v4, v44, v48
	v_add_f32_e32 v5, v45, v49
	v_add_f32_e32 v40, v42, v40
	v_add_f32_e32 v41, v43, v41
	v_lshl_add_u32 v44, v46, 2, 0
	v_add_f32_e32 v4, v4, v40
	v_add_f32_e32 v5, v5, v41
	v_lshl_add_u64 v[2:3], s[10:11], 1, v[2:3]
	v_add_f32_e32 v0, v4, v5
	v_add_u32_e32 v45, 0x12000, v44
	s_nop 0
	v_add_f32_dpp v0, v0, v0 quad_perm:[1,0,3,2] row_mask:0xf bank_mask:0xf bound_ctrl:1
	s_nop 1
	v_add_f32_dpp v0, v0, v0 quad_perm:[2,3,0,1] row_mask:0xf bank_mask:0xf bound_ctrl:1
	s_nop 1
	v_add_f32_dpp v0, v0, v0 row_half_mirror row_mask:0xf bank_mask:0xf bound_ctrl:1
	s_nop 1
	v_add_f32_dpp v0, v0, v0 row_mirror row_mask:0xf bank_mask:0xf bound_ctrl:1
	s_nop 0
	v_readlane_b32 s8, v0, 16
	v_readlane_b32 s9, v0, 48
	v_readlane_b32 s6, v0, 0
	v_readlane_b32 s7, v0, 32
	v_mov_b32_e32 v4, s8
	v_mov_b32_e32 v5, s9
	v_add_f32_e32 v4, s6, v4
	v_add_f32_e32 v5, s7, v5
	s_nop 0
	v_add_f32_e32 v0, v4, v5
	v_fmamk_f32 v0, v0, 0x3a000000, v252
	v_cmp_gt_f32_e32 vcc, s55, v0
	v_mul_f32_e32 v4, 0x4f800000, v0
	s_nop 0
	v_cndmask_b32_e32 v0, v0, v4, vcc
	v_sqrt_f32_e32 v4, v0
	s_nop 0
	v_add_u32_e32 v5, -1, v4
	v_fma_f32 v7, -v5, v4, v0
	v_cmp_ge_f32_e64 s[8:9], 0, v7
	v_add_u32_e32 v7, 1, v4
	s_nop 0
	v_cndmask_b32_e64 v5, v4, v5, s[8:9]
	v_fma_f32 v4, -v7, v4, v0
	v_cmp_lt_f32_e64 s[8:9], 0, v4
	s_nop 1
	v_cndmask_b32_e64 v4, v5, v7, s[8:9]
	v_mul_f32_e32 v5, 0x37800000, v4
	v_cndmask_b32_e32 v4, v4, v5, vcc
	v_cmp_class_f32_e32 vcc, v0, v253
	s_nop 1
	v_cndmask_b32_e32 v0, v4, v0, vcc
	v_div_scale_f32 v4, s[6:7], v0, v0, 1.0
	v_rcp_f32_e32 v5, v4
	s_nop 0
	v_fma_f32 v7, -v4, v5, 1.0
	v_fmac_f32_e32 v5, v7, v5
	v_div_scale_f32 v7, vcc, 1.0, v0, 1.0
	v_mul_f32_e32 v40, v7, v5
	v_fma_f32 v41, -v4, v40, v7
	v_fmac_f32_e32 v40, v41, v5
	v_fma_f32 v4, -v4, v40, v7
	v_div_fmas_f32 v4, v4, v5, v40
	v_div_fixup_f32 v0, v4, v0, 1.0
	v_mov_b32_e32 v7, v1
	v_lshl_add_u64 v[2:3], v[2:3], 0, v[6:7]
	v_mul_f32_e32 v40, v36, v0
	v_mul_f32_e32 v41, v37, v0
	v_mul_f32_e32 v42, v38, v0
	v_mul_f32_e32 v43, v39, v0
	ds_read_b128 v[4:7], v44 offset:32768
	ds_read_b128 v[36:39], v45
	v_mul_f32_e32 v28, v28, v0
	v_mul_f32_e32 v29, v29, v0
	v_mul_f32_e32 v30, v30, v0
	v_mul_f32_e32 v31, v31, v0
	v_mul_f32_e32 v20, v20, v0
	v_mul_f32_e32 v21, v21, v0
	v_mul_f32_e32 v22, v22, v0
	v_mul_f32_e32 v23, v23, v0
	s_waitcnt lgkmcnt(0)
	v_fma_f32 v6, v6, v42, v38
	v_fma_f32 v7, v7, v43, v39
	v_fma_f32 v4, v4, v40, v36
	v_fma_f32 v5, v5, v41, v37
	v_mul_f32_e32 v36, v32, v0
	v_mul_f32_e32 v37, v33, v0
	v_cvt_pk_bf16_f32 v4, v4, v5
	v_cvt_pk_bf16_f32 v5, v6, v7
	global_store_dwordx2 v[2:3], v[4:5], off
	v_mul_f32_e32 v38, v34, v0
	v_mul_f32_e32 v39, v35, v0
	ds_read_b128 v[4:7], v44 offset:33792
	ds_read_b128 v[32:35], v45 offset:1024
	v_mul_f32_e32 v14, v14, v0
	v_mul_f32_e32 v15, v15, v0
	s_waitcnt lgkmcnt(0)
	v_fma_f32 v6, v6, v38, v34
	v_fma_f32 v7, v7, v39, v35
	v_fma_f32 v4, v4, v36, v32
	v_fma_f32 v5, v5, v37, v33
	v_mul_f32_e32 v32, v24, v0
	v_mul_f32_e32 v33, v25, v0
	v_cvt_pk_bf16_f32 v4, v4, v5
	v_cvt_pk_bf16_f32 v5, v6, v7
	global_store_dwordx2 v[2:3], v[4:5], off offset:512
	v_mul_f32_e32 v34, v26, v0
	v_mul_f32_e32 v35, v27, v0
	ds_read_b128 v[4:7], v44 offset:34816
	ds_read_b128 v[24:27], v45 offset:2048
	s_waitcnt lgkmcnt(0)
	v_fma_f32 v6, v6, v34, v26
	v_fma_f32 v7, v7, v35, v27
	v_fma_f32 v4, v4, v32, v24
	v_fma_f32 v5, v5, v33, v25
	s_nop 0
	v_cvt_pk_bf16_f32 v4, v4, v5
	v_cvt_pk_bf16_f32 v5, v6, v7
	global_store_dwordx2 v[2:3], v[4:5], off offset:1024
	ds_read_b128 v[4:7], v44 offset:35840
	ds_read_b128 v[24:27], v45 offset:3072
	s_waitcnt lgkmcnt(0)
	v_fma_f32 v6, v30, v6, v26
	v_fma_f32 v7, v31, v7, v27
	v_fma_f32 v4, v28, v4, v24
	v_fma_f32 v5, v29, v5, v25
	v_mul_f32_e32 v24, v16, v0
	v_mul_f32_e32 v25, v17, v0
	v_cvt_pk_bf16_f32 v4, v4, v5
	v_cvt_pk_bf16_f32 v5, v6, v7
	global_store_dwordx2 v[2:3], v[4:5], off offset:1536
	v_mul_f32_e32 v26, v18, v0
	v_mul_f32_e32 v27, v19, v0
	ds_read_b128 v[4:7], v44 offset:36864
	ds_read_b128 v[16:19], v45 offset:4096
	s_waitcnt lgkmcnt(0)
	v_fma_f32 v6, v26, v6, v18
	v_fma_f32 v7, v27, v7, v19
	v_fma_f32 v4, v24, v4, v16
	v_fma_f32 v5, v25, v5, v17
	s_nop 0
	v_cvt_pk_bf16_f32 v4, v4, v5
	v_cvt_pk_bf16_f32 v5, v6, v7
	global_store_dwordx2 v[2:3], v[4:5], off offset:2048
	ds_read_b128 v[4:7], v44 offset:37888
	ds_read_b128 v[16:19], v45 offset:5120
	s_waitcnt lgkmcnt(0)
	v_fma_f32 v6, v22, v6, v18
	v_fma_f32 v7, v23, v7, v19
	v_fma_f32 v4, v20, v4, v16
	v_fma_f32 v5, v21, v5, v17
	v_mul_f32_e32 v16, v10, v0
	v_mul_f32_e32 v17, v11, v0
	v_cvt_pk_bf16_f32 v4, v4, v5
	v_cvt_pk_bf16_f32 v5, v6, v7
	global_store_dwordx2 v[2:3], v[4:5], off offset:2560
	v_mul_f32_e32 v18, v12, v0
	v_mul_f32_e32 v19, v13, v0
	ds_read_b128 v[4:7], v44 offset:38912
	ds_read_b128 v[10:13], v45 offset:6144
	s_waitcnt lgkmcnt(0)
	v_fma_f32 v6, v18, v6, v12
	v_fma_f32 v7, v19, v7, v13
	v_fma_f32 v4, v16, v4, v10
	v_fma_f32 v5, v17, v5, v11
	v_mul_f32_e32 v12, v8, v0
	v_mul_f32_e32 v13, v9, v0
	v_cvt_pk_bf16_f32 v4, v4, v5
	v_cvt_pk_bf16_f32 v5, v6, v7
	global_store_dwordx2 v[2:3], v[4:5], off offset:3072
	ds_read_b128 v[4:7], v44 offset:39936
	ds_read_b128 v[8:11], v45 offset:7168
	s_waitcnt lgkmcnt(0)
	v_fma_f32 v6, v14, v6, v10
	v_fma_f32 v7, v15, v7, v11
	v_fma_f32 v4, v12, v4, v8
	v_fma_f32 v5, v13, v5, v9
	s_nop 0
	v_cvt_pk_bf16_f32 v4, v4, v5
	v_cvt_pk_bf16_f32 v5, v6, v7
	global_store_dwordx2 v[2:3], v[4:5], off offset:3584

; __device__ __forceinline__ u32x4 pack8(f32x4 v0, f32x4 v1) { u32x4 w; w.x = cvt_pk_bf16(v0[0], v0[1]); w.y = cvt_pk_bf16(v0[2], v0[3]); w.z = cvt_pk_bf16(v1[0], v1[1]); w.w = cvt_pk_bf16(v1[2], v1[3]); return w; }
; __device__ __forceinline__ float fast_sigmoid(float x) { return __builtin_amdgcn_rcpf(1.0f + __expf(-x)); }
; __device__ __forceinline__ f32x4 sigm4(f32x4 v) { const f32x4 t = v * -1.4426950408889634f; f32x4 e = {__builtin_amdgcn_exp2f(t[0]), __builtin_amdgcn_exp2f(t[1]), __builtin_amdgcn_exp2f(t[2]), __builtin_amdgcn_exp2f(t[3])};
;     e = e + 1.0f; return (f32x4){__builtin_amdgcn_rcpf(e[0]), __builtin_amdgcn_rcpf(e[1]), __builtin_amdgcn_rcpf(e[2]), __builtin_amdgcn_rcpf(e[3])}; }
; __device__ __forceinline__ f32x4 silu4(f32x4 v) { return v * sigm4(v); }
;     __device__ __forceinline__ void operator()(const f32x4 (&acc)[2][2][4][2], const Unit& u, int wr, int wc, int fr, int fq) const {
;         const int row0 = u.pm * BM + wr * 64 + fr, col0 = u.pn * HALF + wc * 32 + 8 * fq;
; #pragma unroll
;         for (int ai = 0; ai < 2; ++ai)
; #pragma unroll
;             for (int m = 0; m < 4; ++m) {
;                 const f32x4 h0 = silu4(acc[ai][0][m][0] * pre) * (acc[ai][1][m][0] * pre), h1 = silu4(acc[ai][0][m][1] * pre) * (acc[ai][1][m][1] * pre);
;                 st16(H, (size_t)(row0 + ai * HALF + m * 16) * ldh + col0, pack8(h0, h1));
;             }
;     }
.LBB0_1122:
	v_mul_f32_e32 v142, s96, v126
	v_mul_f32_e32 v143, s96, v127
	v_mul_f32_e32 v144, s96, v124
	v_mul_f32_e32 v145, s96, v125
	v_exp_f32_e32 v142, v142
	v_exp_f32_e32 v143, v143
	v_exp_f32_e32 v144, v144
	v_exp_f32_e32 v145, v145
	v_lshl_add_u32 v141, s24, 8, v136
	v_add_f32_e32 v142, 1.0, v142
	v_add_f32_e32 v143, 1.0, v143
	s_movk_i32 s6, 0x1600
	v_add_f32_e32 v144, 1.0, v144
	v_add_f32_e32 v145, 1.0, v145
	v_rcp_f32_e32 v142, v142
	v_rcp_f32_e32 v143, v143
	v_rcp_f32_e32 v144, v144
	v_rcp_f32_e32 v145, v145
	v_lshl_or_b32 v146, s22, 7, v137
	v_mul_f32_e32 v126, v126, v142
	v_mul_f32_e32 v127, v127, v143
	s_mov_b64 s[22:23], -1
	v_mul_f32_e32 v124, v124, v144
	v_mul_f32_e32 v125, v125, v145
	v_mul_f32_e32 v126, v126, v130
	v_mul_f32_e32 v127, v127, v131
	v_mul_f32_e32 v130, s96, v116
	v_mul_f32_e32 v131, s96, v117
	v_mul_f32_e32 v124, v124, v128
	v_mul_f32_e32 v125, v125, v129
	v_mul_f32_e32 v128, s96, v118
	v_mul_f32_e32 v129, s96, v119
	v_exp_f32_e32 v130, v130
	v_exp_f32_e32 v131, v131
	v_exp_f32_e32 v128, v128
	v_exp_f32_e32 v129, v129
	s_andn2_b64 vcc, exec, s[20:21]
	v_add_f32_e32 v130, 1.0, v130
	v_add_f32_e32 v131, 1.0, v131
	v_add_f32_e32 v128, 1.0, v128
	v_add_f32_e32 v129, 1.0, v129
	v_rcp_f32_e32 v130, v130
	v_rcp_f32_e32 v131, v131
	v_rcp_f32_e32 v128, v128
	v_rcp_f32_e32 v129, v129
	v_mul_f32_e32 v116, v116, v130
	v_mul_f32_e32 v117, v117, v131
	s_nop 0
	v_mul_f32_e32 v116, v116, v120
	v_mul_f32_e32 v117, v117, v121
	v_mul_f32_e32 v118, v118, v128
	v_mul_f32_e32 v119, v119, v129
	v_mul_lo_u32 v128, v141, s6
	v_mul_f32_e32 v122, v118, v122
	v_mul_f32_e32 v123, v119, v123
	v_cvt_pk_bf16_f32 v118, v124, v125
	v_cvt_pk_bf16_f32 v119, v126, v127
	v_cvt_pk_bf16_f32 v120, v116, v117
	v_add_lshl_u32 v116, v128, v146, 1
	v_cvt_pk_bf16_f32 v121, v122, v123
	global_store_dwordx4 v116, v[118:121], s[70:71]
	s_nop 1
	v_mul_f32_e32 v118, s96, v110
	v_mul_f32_e32 v119, s96, v111
	v_mul_f32_e32 v120, s96, v108
	v_mul_f32_e32 v121, s96, v109
	v_exp_f32_e32 v118, v118
	v_exp_f32_e32 v120, v120
	v_exp_f32_e32 v121, v121
	v_exp_f32_e32 v119, v119
	v_add_f32_e32 v120, 1.0, v120
	v_add_f32_e32 v121, 1.0, v121
	v_add_f32_e32 v118, 1.0, v118
	v_add_f32_e32 v119, 1.0, v119
	v_rcp_f32_e32 v120, v120
	v_rcp_f32_e32 v121, v121
	v_rcp_f32_e32 v118, v118
	v_rcp_f32_e32 v119, v119
	v_mul_f32_e32 v108, v108, v120
	v_mul_f32_e32 v109, v109, v121
	s_nop 0
	v_mul_f32_e32 v108, v108, v112
	v_mul_f32_e32 v109, v109, v113
	v_mul_f32_e32 v110, v110, v118
	v_mul_f32_e32 v111, v111, v119
	v_mul_f32_e32 v112, s96, v102
	v_mul_f32_e32 v113, s96, v103
	v_mul_f32_e32 v110, v110, v114
	v_mul_f32_e32 v111, v111, v115
	v_mul_f32_e32 v114, s96, v100
	v_mul_f32_e32 v115, s96, v101
	v_exp_f32_e32 v112, v112
	v_exp_f32_e32 v114, v114
	v_exp_f32_e32 v115, v115
	v_exp_f32_e32 v113, v113
	v_add_f32_e32 v114, 1.0, v114
	v_add_f32_e32 v115, 1.0, v115
	v_add_f32_e32 v112, 1.0, v112
	v_add_f32_e32 v113, 1.0, v113
	v_rcp_f32_e32 v114, v114
	v_rcp_f32_e32 v115, v115
	v_rcp_f32_e32 v112, v112
	v_rcp_f32_e32 v113, v113
	v_mul_f32_e32 v100, v100, v114
	v_mul_f32_e32 v101, v101, v115
	v_mul_f32_e32 v102, v102, v112
	v_mul_f32_e32 v103, v103, v113
	s_nop 0
	v_mul_f32_e32 v106, v102, v106
	v_mul_f32_e32 v107, v103, v107
	v_mul_f32_e32 v102, v100, v104
	v_mul_f32_e32 v103, v101, v105
	v_cvt_pk_bf16_f32 v100, v108, v109
	v_cvt_pk_bf16_f32 v101, v110, v111
	v_add_u32_e32 v104, 0x2c000, v116
	v_cvt_pk_bf16_f32 v102, v102, v103
	v_cvt_pk_bf16_f32 v103, v106, v107
	global_store_dwordx4 v104, v[100:103], s[70:71]
	s_nop 1
	v_mul_f32_e32 v100, s96, v94
	v_mul_f32_e32 v101, s96, v95
	v_mul_f32_e32 v102, s96, v92
	v_mul_f32_e32 v103, s96, v93
	v_exp_f32_e32 v100, v100
	v_exp_f32_e32 v102, v102
	v_exp_f32_e32 v103, v103
	v_exp_f32_e32 v101, v101
	v_add_f32_e32 v102, 1.0, v102
	v_add_f32_e32 v103, 1.0, v103
	v_add_f32_e32 v100, 1.0, v100
	v_add_f32_e32 v101, 1.0, v101
	v_rcp_f32_e32 v102, v102
	v_rcp_f32_e32 v103, v103
	v_rcp_f32_e32 v100, v100
	v_rcp_f32_e32 v101, v101
	v_mul_f32_e32 v92, v92, v102
	v_mul_f32_e32 v93, v93, v103
	s_nop 0
	v_mul_f32_e32 v92, v92, v96
	v_mul_f32_e32 v93, v93, v97
	v_mul_f32_e32 v94, v94, v100
	v_mul_f32_e32 v95, v95, v101
	v_mul_f32_e32 v96, s96, v86
	v_mul_f32_e32 v97, s96, v87
	v_mul_f32_e32 v94, v94, v98
	v_mul_f32_e32 v95, v95, v99
	v_mul_f32_e32 v98, s96, v84
	v_mul_f32_e32 v99, s96, v85
	v_exp_f32_e32 v96, v96
	v_exp_f32_e32 v98, v98
	v_exp_f32_e32 v99, v99
	v_exp_f32_e32 v97, v97
	v_add_f32_e32 v98, 1.0, v98
	v_add_f32_e32 v99, 1.0, v99
	v_add_f32_e32 v96, 1.0, v96
	v_add_f32_e32 v97, 1.0, v97
	v_rcp_f32_e32 v98, v98
	v_rcp_f32_e32 v99, v99
	v_rcp_f32_e32 v96, v96
	v_rcp_f32_e32 v97, v97
	v_mul_f32_e32 v84, v84, v98
	v_mul_f32_e32 v85, v85, v99
	v_mul_f32_e32 v86, v86, v96
	v_mul_f32_e32 v87, v87, v97
	s_nop 0
	v_mul_f32_e32 v90, v86, v90
	v_mul_f32_e32 v91, v87, v91
	v_mul_f32_e32 v86, v84, v88
	v_mul_f32_e32 v87, v85, v89
	v_cvt_pk_bf16_f32 v84, v92, v93
	v_cvt_pk_bf16_f32 v85, v94, v95
	v_add_u32_e32 v88, 0x58000, v116
	v_cvt_pk_bf16_f32 v86, v86, v87
	v_cvt_pk_bf16_f32 v87, v90, v91
	global_store_dwordx4 v88, v[84:87], s[70:71]
	s_nop 1
	v_mul_f32_e32 v84, s96, v78
	v_mul_f32_e32 v85, s96, v79
	v_mul_f32_e32 v86, s96, v76
	v_mul_f32_e32 v87, s96, v77
	v_exp_f32_e32 v84, v84
	v_exp_f32_e32 v86, v86
	v_exp_f32_e32 v87, v87
	v_exp_f32_e32 v85, v85
	v_add_f32_e32 v86, 1.0, v86
	v_add_f32_e32 v87, 1.0, v87
	v_add_f32_e32 v84, 1.0, v84
	v_add_f32_e32 v85, 1.0, v85
	v_rcp_f32_e32 v86, v86
	v_rcp_f32_e32 v87, v87
	v_rcp_f32_e32 v84, v84
	v_rcp_f32_e32 v85, v85
	v_mul_f32_e32 v76, v76, v86
	v_mul_f32_e32 v77, v77, v87
	s_nop 0
	v_mul_f32_e32 v76, v76, v80
; __device__ __forceinline__ u32x4 pack8(f32x4 v0, f32x4 v1) { u32x4 w; w.x = cvt_pk_bf16(v0[0], v0[1]); w.y = cvt_pk_bf16(v0[2], v0[3]); w.z = cvt_pk_bf16(v1[0], v1[1]); w.w = cvt_pk_bf16(v1[2], v1[3]); return w; }
; __device__ __forceinline__ float fast_sigmoid(float x) { return __builtin_amdgcn_rcpf(1.0f + __expf(-x)); }
; __device__ __forceinline__ f32x4 sigm4(f32x4 v) { const f32x4 t = v * -1.4426950408889634f; f32x4 e = {__builtin_amdgcn_exp2f(t[0]), __builtin_amdgcn_exp2f(t[1]), __builtin_amdgcn_exp2f(t[2]), __builtin_amdgcn_exp2f(t[3])};
;     e = e + 1.0f; return (f32x4){__builtin_amdgcn_rcpf(e[0]), __builtin_amdgcn_rcpf(e[1]), __builtin_amdgcn_rcpf(e[2]), __builtin_amdgcn_rcpf(e[3])}; }
; __device__ __forceinline__ f32x4 silu4(f32x4 v) { return v * sigm4(v); }
;     __device__ __forceinline__ void operator()(const f32x4 (&acc)[2][2][4][2], const Unit& u, int wr, int wc, int fr, int fq) const {
;         const int row0 = u.pm * BM + wr * 64 + fr, col0 = u.pn * HALF + wc * 32 + 8 * fq;
; #pragma unroll
;         for (int ai = 0; ai < 2; ++ai)
; #pragma unroll
;             for (int m = 0; m < 4; ++m) {
;                 const f32x4 h0 = silu4(acc[ai][0][m][0] * pre) * (acc[ai][1][m][0] * pre), h1 = silu4(acc[ai][0][m][1] * pre) * (acc[ai][1][m][1] * pre);
;                 st16(H, (size_t)(row0 + ai * HALF + m * 16) * ldh + col0, pack8(h0, h1));
;             }
;     }
	v_mul_f32_e32 v77, v77, v81
	v_mul_f32_e32 v78, v78, v84
	v_mul_f32_e32 v79, v79, v85
	v_mul_f32_e32 v80, s96, v62
	v_mul_f32_e32 v81, s96, v63
	v_mul_f32_e32 v78, v78, v82
	v_mul_f32_e32 v79, v79, v83
	v_mul_f32_e32 v82, s96, v60
	v_mul_f32_e32 v83, s96, v61
	v_exp_f32_e32 v80, v80
	v_exp_f32_e32 v82, v82
	v_exp_f32_e32 v83, v83
	v_exp_f32_e32 v81, v81
	v_add_f32_e32 v82, 1.0, v82
	v_add_f32_e32 v83, 1.0, v83
	v_add_f32_e32 v80, 1.0, v80
	v_add_f32_e32 v81, 1.0, v81
	v_rcp_f32_e32 v82, v82
	v_rcp_f32_e32 v83, v83
	v_rcp_f32_e32 v80, v80
	v_rcp_f32_e32 v81, v81
	v_mul_f32_e32 v60, v60, v82
	v_mul_f32_e32 v61, v61, v83
	v_mul_f32_e32 v62, v62, v80
	v_mul_f32_e32 v63, v63, v81
	s_nop 0
	v_mul_f32_e32 v70, v62, v70
	v_mul_f32_e32 v71, v63, v71
	v_mul_f32_e32 v62, v60, v68
	v_mul_f32_e32 v63, v61, v69
	v_cvt_pk_bf16_f32 v60, v76, v77
	v_cvt_pk_bf16_f32 v61, v78, v79
	v_add_u32_e32 v68, 0x84000, v116
	v_cvt_pk_bf16_f32 v62, v62, v63
	v_cvt_pk_bf16_f32 v63, v70, v71
	global_store_dwordx4 v68, v[60:63], s[70:71]
	s_nop 1
	v_mul_f32_e32 v60, s96, v66
	v_mul_f32_e32 v61, s96, v67
	v_mul_f32_e32 v62, s96, v64
	v_mul_f32_e32 v63, s96, v65
	v_exp_f32_e32 v60, v60
	v_exp_f32_e32 v62, v62
	v_exp_f32_e32 v63, v63
	v_exp_f32_e32 v61, v61
	v_add_f32_e32 v62, 1.0, v62
	v_add_f32_e32 v63, 1.0, v63
	v_add_f32_e32 v60, 1.0, v60
	v_add_f32_e32 v61, 1.0, v61
	v_rcp_f32_e32 v62, v62
	v_rcp_f32_e32 v63, v63
	v_rcp_f32_e32 v60, v60
	v_rcp_f32_e32 v61, v61
	v_mul_f32_e32 v62, v64, v62
	v_mul_f32_e32 v63, v65, v63
	v_mul_f32_e32 v64, s96, v54
	v_mul_f32_e32 v65, s96, v55
	v_mul_f32_e32 v60, v66, v60
	v_mul_f32_e32 v61, v67, v61
	v_mul_f32_e32 v66, s96, v52
	v_mul_f32_e32 v67, s96, v53
	v_exp_f32_e32 v64, v64
	v_exp_f32_e32 v66, v66
	v_exp_f32_e32 v67, v67
	v_exp_f32_e32 v65, v65
	v_mul_f32_e32 v60, v60, v74
	v_mul_f32_e32 v61, v61, v75
	v_mul_f32_e32 v62, v62, v72
	v_mul_f32_e32 v63, v63, v73
	v_add_f32_e32 v66, 1.0, v66
	v_add_f32_e32 v67, 1.0, v67
	v_add_f32_e32 v64, 1.0, v64
	v_add_f32_e32 v65, 1.0, v65
	v_rcp_f32_e32 v66, v66
	v_rcp_f32_e32 v67, v67
	v_rcp_f32_e32 v64, v64
	v_rcp_f32_e32 v65, v65
	v_mul_f32_e32 v52, v52, v66
	v_mul_f32_e32 v53, v53, v67
	v_mul_f32_e32 v54, v54, v64
	v_mul_f32_e32 v55, v55, v65
	s_nop 0
	v_mul_f32_e32 v58, v54, v58
	v_mul_f32_e32 v59, v55, v59
	v_mul_f32_e32 v54, v52, v56
	v_mul_f32_e32 v55, v53, v57
	v_cvt_pk_bf16_f32 v52, v62, v63
	v_cvt_pk_bf16_f32 v53, v60, v61
	v_add_u32_e32 v56, 0x160000, v116
	v_cvt_pk_bf16_f32 v54, v54, v55
	v_cvt_pk_bf16_f32 v55, v58, v59
	global_store_dwordx4 v56, v[52:55], s[70:71]
	s_nop 1
	v_mul_f32_e32 v52, s96, v46
	v_mul_f32_e32 v53, s96, v47
	v_mul_f32_e32 v54, s96, v44
	v_mul_f32_e32 v55, s96, v45
	v_exp_f32_e32 v52, v52
	v_exp_f32_e32 v54, v54
	v_exp_f32_e32 v55, v55
	v_exp_f32_e32 v53, v53
	v_add_f32_e32 v54, 1.0, v54
	v_add_f32_e32 v55, 1.0, v55
	v_add_f32_e32 v52, 1.0, v52
	v_add_f32_e32 v53, 1.0, v53
	v_rcp_f32_e32 v54, v54
	v_rcp_f32_e32 v55, v55
	v_rcp_f32_e32 v52, v52
	v_rcp_f32_e32 v53, v53
	v_mul_f32_e32 v44, v44, v54
	v_mul_f32_e32 v45, v45, v55
	s_nop 0
	v_mul_f32_e32 v44, v44, v48
	v_mul_f32_e32 v45, v45, v49
	v_mul_f32_e32 v46, v46, v52
	v_mul_f32_e32 v47, v47, v53
	v_mul_f32_e32 v48, s96, v38
	v_mul_f32_e32 v49, s96, v39
	v_mul_f32_e32 v46, v46, v50
	v_mul_f32_e32 v47, v47, v51
	v_mul_f32_e32 v50, s96, v36
	v_mul_f32_e32 v51, s96, v37
	v_exp_f32_e32 v48, v48
	v_exp_f32_e32 v50, v50
	v_exp_f32_e32 v51, v51
	v_exp_f32_e32 v49, v49
	v_add_f32_e32 v50, 1.0, v50
	v_add_f32_e32 v51, 1.0, v51
	v_add_f32_e32 v48, 1.0, v48
	v_add_f32_e32 v49, 1.0, v49
	v_rcp_f32_e32 v50, v50
	v_rcp_f32_e32 v51, v51
	v_rcp_f32_e32 v48, v48
	v_rcp_f32_e32 v49, v49
; __device__ __forceinline__ u32x4 pack8(f32x4 v0, f32x4 v1) { u32x4 w; w.x = cvt_pk_bf16(v0[0], v0[1]); w.y = cvt_pk_bf16(v0[2], v0[3]); w.z = cvt_pk_bf16(v1[0], v1[1]); w.w = cvt_pk_bf16(v1[2], v1[3]); return w; }
; __device__ __forceinline__ float fast_sigmoid(float x) { return __builtin_amdgcn_rcpf(1.0f + __expf(-x)); }
; __device__ __forceinline__ f32x4 sigm4(f32x4 v) { const f32x4 t = v * -1.4426950408889634f; f32x4 e = {__builtin_amdgcn_exp2f(t[0]), __builtin_amdgcn_exp2f(t[1]), __builtin_amdgcn_exp2f(t[2]), __builtin_amdgcn_exp2f(t[3])};
;     e = e + 1.0f; return (f32x4){__builtin_amdgcn_rcpf(e[0]), __builtin_amdgcn_rcpf(e[1]), __builtin_amdgcn_rcpf(e[2]), __builtin_amdgcn_rcpf(e[3])}; }
; __device__ __forceinline__ f32x4 silu4(f32x4 v) { return v * sigm4(v); }
;     __device__ __forceinline__ void operator()(const f32x4 (&acc)[2][2][4][2], const Unit& u, int wr, int wc, int fr, int fq) const {
;         const int row0 = u.pm * BM + wr * 64 + fr, col0 = u.pn * HALF + wc * 32 + 8 * fq;
; #pragma unroll
;         for (int ai = 0; ai < 2; ++ai)
; #pragma unroll
;             for (int m = 0; m < 4; ++m) {
;                 const f32x4 h0 = silu4(acc[ai][0][m][0] * pre) * (acc[ai][1][m][0] * pre), h1 = silu4(acc[ai][0][m][1] * pre) * (acc[ai][1][m][1] * pre);
;                 st16(H, (size_t)(row0 + ai * HALF + m * 16) * ldh + col0, pack8(h0, h1));
;             }
;     }
	v_mul_f32_e32 v36, v36, v50
	v_mul_f32_e32 v37, v37, v51
	v_mul_f32_e32 v38, v38, v48
	v_mul_f32_e32 v39, v39, v49
	s_nop 0
	v_mul_f32_e32 v42, v38, v42
	v_mul_f32_e32 v43, v39, v43
	v_mul_f32_e32 v38, v36, v40
	v_mul_f32_e32 v39, v37, v41
	v_cvt_pk_bf16_f32 v36, v44, v45
	v_cvt_pk_bf16_f32 v37, v46, v47
	v_add_u32_e32 v40, 0x18c000, v116
	v_cvt_pk_bf16_f32 v38, v38, v39
	v_cvt_pk_bf16_f32 v39, v42, v43
	global_store_dwordx4 v40, v[36:39], s[70:71]
	s_nop 1
	v_mul_f32_e32 v36, s96, v30
	v_mul_f32_e32 v37, s96, v31
	v_mul_f32_e32 v38, s96, v28
	v_mul_f32_e32 v39, s96, v29
	v_exp_f32_e32 v36, v36
	v_exp_f32_e32 v38, v38
	v_exp_f32_e32 v39, v39
	v_exp_f32_e32 v37, v37
	v_add_f32_e32 v38, 1.0, v38
	v_add_f32_e32 v39, 1.0, v39
	v_add_f32_e32 v36, 1.0, v36
	v_add_f32_e32 v37, 1.0, v37
	v_rcp_f32_e32 v38, v38
	v_rcp_f32_e32 v39, v39
	v_rcp_f32_e32 v36, v36
	v_rcp_f32_e32 v37, v37
	v_mul_f32_e32 v28, v28, v38
	v_mul_f32_e32 v29, v29, v39
	s_nop 0
	v_mul_f32_e32 v28, v28, v32
	v_mul_f32_e32 v29, v29, v33
	v_mul_f32_e32 v30, v30, v36
	v_mul_f32_e32 v31, v31, v37
	v_mul_f32_e32 v32, s96, v22
	v_mul_f32_e32 v33, s96, v23
	v_mul_f32_e32 v30, v30, v34
	v_mul_f32_e32 v31, v31, v35
	v_mul_f32_e32 v34, s96, v20
	v_mul_f32_e32 v35, s96, v21
	v_exp_f32_e32 v32, v32
	v_exp_f32_e32 v34, v34
	v_exp_f32_e32 v35, v35
	v_exp_f32_e32 v33, v33
	v_add_f32_e32 v34, 1.0, v34
	v_add_f32_e32 v35, 1.0, v35
	v_add_f32_e32 v32, 1.0, v32
	v_add_f32_e32 v33, 1.0, v33
	v_rcp_f32_e32 v34, v34
	v_rcp_f32_e32 v35, v35
	v_rcp_f32_e32 v32, v32
	v_rcp_f32_e32 v33, v33
	v_mul_f32_e32 v20, v20, v34
	v_mul_f32_e32 v21, v21, v35
	v_mul_f32_e32 v22, v22, v32
	v_mul_f32_e32 v23, v23, v33
	s_nop 0
	v_mul_f32_e32 v26, v22, v26
	v_mul_f32_e32 v27, v23, v27
	v_mul_f32_e32 v22, v20, v24
	v_mul_f32_e32 v23, v21, v25
	v_cvt_pk_bf16_f32 v20, v28, v29
	v_cvt_pk_bf16_f32 v21, v30, v31
	v_add_u32_e32 v24, 0x1b8000, v116
	v_cvt_pk_bf16_f32 v22, v22, v23
	v_cvt_pk_bf16_f32 v23, v26, v27
	global_store_dwordx4 v24, v[20:23], s[70:71]
	s_nop 1
	v_mul_f32_e32 v20, s96, v14
	v_mul_f32_e32 v21, s96, v15
	v_mul_f32_e32 v22, s96, v12
	v_mul_f32_e32 v23, s96, v13
	v_exp_f32_e32 v20, v20
	v_exp_f32_e32 v22, v22
	v_exp_f32_e32 v23, v23
	v_exp_f32_e32 v21, v21
	v_add_f32_e32 v22, 1.0, v22
	v_add_f32_e32 v23, 1.0, v23
	v_add_f32_e32 v20, 1.0, v20
	v_add_f32_e32 v21, 1.0, v21
	v_rcp_f32_e32 v22, v22
	v_rcp_f32_e32 v23, v23
	v_rcp_f32_e32 v20, v20
	v_rcp_f32_e32 v21, v21
	v_mul_f32_e32 v12, v12, v22
	v_mul_f32_e32 v13, v13, v23
	s_nop 0
	v_mul_f32_e32 v12, v12, v16
	v_mul_f32_e32 v13, v13, v17
	v_mul_f32_e32 v14, v14, v20
	v_mul_f32_e32 v15, v15, v21
	v_mul_f32_e32 v16, s96, v6
	v_mul_f32_e32 v17, s96, v7
	v_mul_f32_e32 v14, v14, v18
	v_mul_f32_e32 v15, v15, v19
	v_mul_f32_e32 v18, s96, v4
	v_mul_f32_e32 v19, s96, v5
	v_exp_f32_e32 v16, v16
	v_exp_f32_e32 v18, v18
	v_exp_f32_e32 v19, v19
	v_exp_f32_e32 v17, v17
	v_add_f32_e32 v18, 1.0, v18
	v_add_f32_e32 v19, 1.0, v19
	v_add_f32_e32 v16, 1.0, v16
	v_add_f32_e32 v17, 1.0, v17
	v_rcp_f32_e32 v18, v18
	v_rcp_f32_e32 v19, v19
	v_rcp_f32_e32 v16, v16
	v_rcp_f32_e32 v17, v17
	v_mul_f32_e32 v4, v4, v18
	v_mul_f32_e32 v5, v5, v19
	v_mul_f32_e32 v6, v6, v16
	v_mul_f32_e32 v7, v7, v17
	s_nop 0
	v_mul_f32_e32 v10, v6, v10
	v_mul_f32_e32 v11, v7, v11
	v_mul_f32_e32 v6, v4, v8
	v_mul_f32_e32 v7, v5, v9
	v_add_u32_e32 v8, 0x1e4000, v116
	v_cvt_pk_bf16_f32 v4, v12, v13
	v_cvt_pk_bf16_f32 v5, v14, v15
	v_cvt_pk_bf16_f32 v6, v6, v7
	v_cvt_pk_bf16_f32 v7, v10, v11
	global_store_dwordx4 v8, v[4:7], s[70:71]
	s_cbranch_vccnz .LBB0_1110
	s_andn2_b64 vcc, exec, s[8:9]
	s_cbranch_vccnz .LBB0_1109
	s_barrier
	s_branch .LBB0_1109

.LBB0_1226:
	v_add_u32_e32 v0, 0x10000, v186
	v_add_u32_e32 v188, 0x14000, v186
	ds_read_b128 v[112:115], v0
	ds_read_b128 v[120:123], v0 offset:1024
	ds_read_b128 v[124:127], v0 offset:2048
	ds_read_b128 v[132:135], v0 offset:3072
	ds_read_b128 v[148:151], v188
	ds_read_b128 v[152:155], v188 offset:1024
	ds_read_b128 v[156:159], v188 offset:2048
	ds_read_b128 v[160:163], v188 offset:3072
	s_add_u32 s14, s12, 0xffea0080
	s_addc_u32 s15, s13, -1
	s_cmpk_eq_i32 s52, 0x54
	s_cselect_b32 s18, s8, s14
	s_cselect_b32 s19, s9, s15
	s_cselect_b32 s16, s6, s53
	s_cselect_b32 s17, s7, s57
	s_add_u32 s14, s18, 0x80
	s_addc_u32 s15, s19, 0
	ds_read_b128 v[164:167], v187
	ds_read_b128 v[168:171], v187 offset:1024
	ds_read_b128 v[178:181], v187 offset:2048
	ds_read_b128 v[190:193], v187 offset:3072
	ds_read_b128 v[194:197], v187 offset:4096
	ds_read_b128 v[198:201], v187 offset:5120
	ds_read_b128 v[202:205], v187 offset:6144
	ds_read_b128 v[206:209], v187 offset:7168
	s_mov_b32 m0, s44
	s_nop 0
	global_load_lds_dwordx4 v174, s[12:13]
	s_nop 0
	s_mov_b32 m0, s45
	s_nop 0
	global_load_lds_dwordx4 v176, s[12:13]
	s_waitcnt vmcnt(8)
	s_waitcnt lgkmcnt(0)
	s_barrier
	s_setprio 1
	s_waitcnt lgkmcnt(0)
	v_mfma_f32_16x16x32_bf16 v[144:147], v[112:115], v[164:167], v[144:147]
	v_mfma_f32_16x16x32_bf16 v[140:143], v[124:127], v[164:167], v[140:143]
	s_waitcnt lgkmcnt(5)
	v_mfma_f32_16x16x32_bf16 v[116:119], v[112:115], v[178:181], v[116:119]
	v_mfma_f32_16x16x32_bf16 v[108:111], v[124:127], v[178:181], v[108:111]
	s_waitcnt lgkmcnt(3)
	v_mfma_f32_16x16x32_bf16 v[96:99], v[112:115], v[194:197], v[96:99]
	v_mfma_f32_16x16x32_bf16 v[92:95], v[124:127], v[194:197], v[92:95]
	s_waitcnt lgkmcnt(1)
	v_mfma_f32_16x16x32_bf16 v[80:83], v[112:115], v[202:205], v[80:83]
	v_mfma_f32_16x16x32_bf16 v[76:79], v[124:127], v[202:205], v[76:79]
	v_mfma_f32_16x16x32_bf16 v[144:147], v[120:123], v[168:171], v[144:147]
	v_mfma_f32_16x16x32_bf16 v[140:143], v[132:135], v[168:171], v[140:143]
	v_mfma_f32_16x16x32_bf16 v[116:119], v[120:123], v[190:193], v[116:119]
	v_mfma_f32_16x16x32_bf16 v[108:111], v[132:135], v[190:193], v[108:111]
	v_mfma_f32_16x16x32_bf16 v[96:99], v[120:123], v[198:201], v[96:99]
	v_mfma_f32_16x16x32_bf16 v[92:95], v[132:135], v[198:201], v[92:95]
	s_waitcnt lgkmcnt(0)
	v_mfma_f32_16x16x32_bf16 v[80:83], v[120:123], v[206:209], v[80:83]
	v_mfma_f32_16x16x32_bf16 v[76:79], v[132:135], v[206:209], v[76:79]
	s_setprio 0
	s_setprio 1
	v_mfma_f32_16x16x32_bf16 v[136:139], v[148:151], v[164:167], v[136:139]
	v_mfma_f32_16x16x32_bf16 v[128:131], v[156:159], v[164:167], v[128:131]
	v_mfma_f32_16x16x32_bf16 v[104:107], v[148:151], v[178:181], v[104:107]
	v_mfma_f32_16x16x32_bf16 v[100:103], v[156:159], v[178:181], v[100:103]
	v_mfma_f32_16x16x32_bf16 v[88:91], v[148:151], v[194:197], v[88:91]
	v_mfma_f32_16x16x32_bf16 v[84:87], v[156:159], v[194:197], v[84:87]
	v_mfma_f32_16x16x32_bf16 v[72:75], v[148:151], v[202:205], v[72:75]
	v_mfma_f32_16x16x32_bf16 v[68:71], v[156:159], v[202:205], v[68:71]
	v_mfma_f32_16x16x32_bf16 v[136:139], v[152:155], v[168:171], v[136:139]
	v_mfma_f32_16x16x32_bf16 v[128:131], v[160:163], v[168:171], v[128:131]
	v_mfma_f32_16x16x32_bf16 v[104:107], v[152:155], v[190:193], v[104:107]
	v_mfma_f32_16x16x32_bf16 v[100:103], v[160:163], v[190:193], v[100:103]
	v_mfma_f32_16x16x32_bf16 v[88:91], v[152:155], v[198:201], v[88:91]
	v_mfma_f32_16x16x32_bf16 v[84:87], v[160:163], v[198:201], v[84:87]
	v_mfma_f32_16x16x32_bf16 v[72:75], v[152:155], v[206:209], v[72:75]
	v_mfma_f32_16x16x32_bf16 v[68:71], v[160:163], v[206:209], v[68:71]
	s_setprio 0
	s_barrier
	ds_read_b128 v[164:167], v187 offset:16384
	ds_read_b128 v[168:171], v187 offset:17408
	ds_read_b128 v[178:181], v187 offset:18432
	ds_read_b128 v[190:193], v187 offset:19456
	ds_read_b128 v[194:197], v187 offset:20480
	ds_read_b128 v[198:201], v187 offset:21504
	ds_read_b128 v[202:205], v187 offset:22528
	ds_read_b128 v[206:209], v187 offset:23552
	s_mov_b32 m0, s22
	s_nop 0
	global_load_lds_dwordx4 v175, s[16:17]
	s_add_u32 s78, s16, 0x160000
	s_mov_b32 m0, s23
	s_nop 0
	global_load_lds_dwordx4 v177, s[16:17]
	s_addc_u32 s79, s17, 0
	s_mov_b32 m0, s26
	s_nop 0
	global_load_lds_dwordx4 v175, s[78:79]
	s_nop 0
	s_mov_b32 m0, s27
	s_nop 0
	global_load_lds_dwordx4 v177, s[78:79]
	s_nop 0
	s_mov_b32 m0, s21
	s_nop 0
	global_load_lds_dwordx4 v174, s[18:19]
	s_nop 0
	s_mov_b32 m0, s28
	s_nop 0
	global_load_lds_dwordx4 v176, s[18:19]
	s_waitcnt vmcnt(8)
	s_waitcnt lgkmcnt(0)
	s_barrier
	s_setprio 1
	s_waitcnt lgkmcnt(0)
	v_mfma_f32_16x16x32_bf16 v[64:67], v[112:115], v[164:167], v[64:67]
	v_mfma_f32_16x16x32_bf16 v[60:63], v[124:127], v[164:167], v[60:63]
	s_waitcnt lgkmcnt(5)
	v_mfma_f32_16x16x32_bf16 v[48:51], v[112:115], v[178:181], v[48:51]
	v_mfma_f32_16x16x32_bf16 v[44:47], v[124:127], v[178:181], v[44:47]
	s_waitcnt lgkmcnt(3)
	v_mfma_f32_16x16x32_bf16 v[32:35], v[112:115], v[194:197], v[32:35]
	v_mfma_f32_16x16x32_bf16 v[28:31], v[124:127], v[194:197], v[28:31]
	s_waitcnt lgkmcnt(1)
	v_mfma_f32_16x16x32_bf16 v[16:19], v[112:115], v[202:205], v[16:19]
	v_mfma_f32_16x16x32_bf16 v[12:15], v[124:127], v[202:205], v[12:15]
	v_mfma_f32_16x16x32_bf16 v[64:67], v[120:123], v[168:171], v[64:67]
	v_mfma_f32_16x16x32_bf16 v[60:63], v[132:135], v[168:171], v[60:63]
	v_mfma_f32_16x16x32_bf16 v[48:51], v[120:123], v[190:193], v[48:51]
	v_mfma_f32_16x16x32_bf16 v[44:47], v[132:135], v[190:193], v[44:47]
	v_mfma_f32_16x16x32_bf16 v[32:35], v[120:123], v[198:201], v[32:35]
	v_mfma_f32_16x16x32_bf16 v[28:31], v[132:135], v[198:201], v[28:31]
	s_waitcnt lgkmcnt(0)
	v_mfma_f32_16x16x32_bf16 v[16:19], v[120:123], v[206:209], v[16:19]
	v_mfma_f32_16x16x32_bf16 v[12:15], v[132:135], v[206:209], v[12:15]
	s_setprio 0
	s_setprio 1
	v_mfma_f32_16x16x32_bf16 v[56:59], v[148:151], v[164:167], v[56:59]
	v_mfma_f32_16x16x32_bf16 v[52:55], v[156:159], v[164:167], v[52:55]
	v_mfma_f32_16x16x32_bf16 v[40:43], v[148:151], v[178:181], v[40:43]
	v_mfma_f32_16x16x32_bf16 v[36:39], v[156:159], v[178:181], v[36:39]
	v_mfma_f32_16x16x32_bf16 v[24:27], v[148:151], v[194:197], v[24:27]
	v_mfma_f32_16x16x32_bf16 v[20:23], v[156:159], v[194:197], v[20:23]
	v_mfma_f32_16x16x32_bf16 v[8:11], v[148:151], v[202:205], v[8:11]
	v_mfma_f32_16x16x32_bf16 v[2:5], v[156:159], v[202:205], v[4:7]
	v_mfma_f32_16x16x32_bf16 v[56:59], v[152:155], v[168:171], v[56:59]
	v_mfma_f32_16x16x32_bf16 v[52:55], v[160:163], v[168:171], v[52:55]
	v_mfma_f32_16x16x32_bf16 v[40:43], v[152:155], v[190:193], v[40:43]
	v_mfma_f32_16x16x32_bf16 v[36:39], v[160:163], v[190:193], v[36:39]
	v_mfma_f32_16x16x32_bf16 v[24:27], v[152:155], v[198:201], v[24:27]
	v_mfma_f32_16x16x32_bf16 v[20:23], v[160:163], v[198:201], v[20:23]
	v_mfma_f32_16x16x32_bf16 v[8:11], v[152:155], v[206:209], v[8:11]
	v_mfma_f32_16x16x32_bf16 v[2:5], v[160:163], v[206:209], v[2:5]
	s_setprio 0
	s_barrier
	v_add_u32_e32 v189, 0x18000, v186
	v_add_u32_e32 v190, 0x1c000, v186
	ds_read_b128 v[112:115], v189
	ds_read_b128 v[120:123], v189 offset:1024
	ds_read_b128 v[124:127], v189 offset:2048
	ds_read_b128 v[132:135], v189 offset:3072
	ds_read_b128 v[148:151], v190
	ds_read_b128 v[152:155], v190 offset:1024
	ds_read_b128 v[156:159], v190 offset:2048
	ds_read_b128 v[160:163], v190 offset:3072
	ds_read_b128 v[164:167], v187 offset:32768
	ds_read_b128 v[168:171], v187 offset:33792
	ds_read_b128 v[178:181], v187 offset:34816
	ds_read_b128 v[192:195], v187 offset:35840
	ds_read_b128 v[196:199], v187 offset:36864
	ds_read_b128 v[200:203], v187 offset:37888
	ds_read_b128 v[204:207], v187 offset:38912
	ds_read_b128 v[208:211], v187 offset:39936
	s_add_u32 s18, s18, 0x160000
	s_addc_u32 s19, s19, 0
	s_mov_b32 m0, s29
	s_nop 0
	global_load_lds_dwordx4 v174, s[18:19]
	s_nop 0
	s_mov_b32 m0, s30
	s_nop 0
	global_load_lds_dwordx4 v176, s[18:19]
	s_waitcnt vmcnt(8)
	s_waitcnt lgkmcnt(0)
	s_barrier
	s_setprio 1
	s_waitcnt lgkmcnt(0)
	v_mfma_f32_16x16x32_bf16 v[144:147], v[112:115], v[164:167], v[144:147]
	v_mfma_f32_16x16x32_bf16 v[140:143], v[124:127], v[164:167], v[140:143]
	s_waitcnt lgkmcnt(5)
	v_mfma_f32_16x16x32_bf16 v[116:119], v[112:115], v[178:181], v[116:119]
	v_mfma_f32_16x16x32_bf16 v[108:111], v[124:127], v[178:181], v[108:111]
	s_waitcnt lgkmcnt(3)
	v_mfma_f32_16x16x32_bf16 v[96:99], v[112:115], v[196:199], v[96:99]
	v_mfma_f32_16x16x32_bf16 v[92:95], v[124:127], v[196:199], v[92:95]
	s_waitcnt lgkmcnt(1)
	v_mfma_f32_16x16x32_bf16 v[80:83], v[112:115], v[204:207], v[80:83]
	v_mfma_f32_16x16x32_bf16 v[76:79], v[124:127], v[204:207], v[76:79]
	v_mfma_f32_16x16x32_bf16 v[144:147], v[120:123], v[168:171], v[144:147]
	v_mfma_f32_16x16x32_bf16 v[140:143], v[132:135], v[168:171], v[140:143]
	v_mfma_f32_16x16x32_bf16 v[116:119], v[120:123], v[192:195], v[116:119]
	v_mfma_f32_16x16x32_bf16 v[108:111], v[132:135], v[192:195], v[108:111]
	v_mfma_f32_16x16x32_bf16 v[96:99], v[120:123], v[200:203], v[96:99]
	v_mfma_f32_16x16x32_bf16 v[92:95], v[132:135], v[200:203], v[92:95]
	s_waitcnt lgkmcnt(0)
	v_mfma_f32_16x16x32_bf16 v[80:83], v[120:123], v[208:211], v[80:83]
	v_mfma_f32_16x16x32_bf16 v[76:79], v[132:135], v[208:211], v[76:79]
	s_setprio 0
	s_setprio 1
	v_mfma_f32_16x16x32_bf16 v[136:139], v[148:151], v[164:167], v[136:139]
	v_mfma_f32_16x16x32_bf16 v[128:131], v[156:159], v[164:167], v[128:131]
	v_mfma_f32_16x16x32_bf16 v[104:107], v[148:151], v[178:181], v[104:107]
	v_mfma_f32_16x16x32_bf16 v[100:103], v[156:159], v[178:181], v[100:103]
	v_mfma_f32_16x16x32_bf16 v[88:91], v[148:151], v[196:199], v[88:91]
	v_mfma_f32_16x16x32_bf16 v[84:87], v[156:159], v[196:199], v[84:87]
	v_mfma_f32_16x16x32_bf16 v[72:75], v[148:151], v[204:207], v[72:75]
	v_mfma_f32_16x16x32_bf16 v[68:71], v[156:159], v[204:207], v[68:71]
	v_mfma_f32_16x16x32_bf16 v[136:139], v[152:155], v[168:171], v[136:139]
	v_mfma_f32_16x16x32_bf16 v[128:131], v[160:163], v[168:171], v[128:131]
	v_mfma_f32_16x16x32_bf16 v[104:107], v[152:155], v[192:195], v[104:107]
	v_mfma_f32_16x16x32_bf16 v[100:103], v[160:163], v[192:195], v[100:103]
	v_mfma_f32_16x16x32_bf16 v[88:91], v[152:155], v[200:203], v[88:91]
	v_mfma_f32_16x16x32_bf16 v[84:87], v[160:163], v[200:203], v[84:87]
	v_mfma_f32_16x16x32_bf16 v[72:75], v[152:155], v[208:211], v[72:75]
	v_mfma_f32_16x16x32_bf16 v[68:71], v[160:163], v[208:211], v[68:71]
	s_setprio 0
	s_barrier
; #define ER_LOAD(dst, ai, mp) do { _Pragma("unroll") for (int mm = 0; mm < 2; ++mm) _Pragma("unroll") for (int bj = 0; bj < 2; ++bj) \
;             dst[mm][bj] = *(const u32x4*)(xb + (size_t)((ai) * HALF + (2 * (mp) + mm) * 16) * 2048 + bj * HALF); } while (0)
;     __device__ __forceinline__ void operator()(const f32x4 (&acc)[2][2][4][2], const Unit& u, int wr, int wc, int fr, int fq) const {
;         const int row0 = u.pm * BM + wr * 64 + fr, col0 = u.pn * BM + wc * 32 + 8 * fq;
;         const int b = (u.pm < n_lat_panels) ? (u.pm >> 4) : 4;
;         const float* g = gate + (size_t)b * gstride + col0;
;         bf16_t* xb = X + (size_t)row0 * 2048 + col0;
;         f32x4 gv[2][2];
; #pragma unroll
;         for (int bj = 0; bj < 2; ++bj)
; #pragma unroll
;             for (int n = 0; n < 2; ++n) gv[bj][n] = *(const f32x4*)(g + bj * HALF + 4 * n);
;         u32x4 xa[2][2], xc[2][2];
;     ...
;         ER_LOAD(xa, 0, 0); ER_LOAD(xc, 0, 1);
	ds_read_b128 v[164:167], v187 offset:49152
	ds_read_b128 v[168:171], v187 offset:50176
	ds_read_b128 v[178:181], v187 offset:51200
	ds_read_b128 v[192:195], v187 offset:52224
	ds_read_b128 v[196:199], v187 offset:53248
	ds_read_b128 v[200:203], v187 offset:54272
	ds_read_b128 v[204:207], v187 offset:55296
	ds_read_b128 v[208:211], v187 offset:56320
	s_add_u32 s18, s16, 0x80
	s_addc_u32 s19, s17, 0
	s_mov_b32 m0, s34
	s_nop 0
	global_load_lds_dwordx4 v175, s[18:19]
	s_add_u32 s16, s16, 0x160080
	s_mov_b32 m0, s35
	s_nop 0
	global_load_lds_dwordx4 v177, s[18:19]
	s_addc_u32 s17, s17, 0
	s_mov_b32 m0, s40
	s_nop 0
	global_load_lds_dwordx4 v175, s[16:17]
	s_nop 0
	s_mov_b32 m0, s41
	s_nop 0
	global_load_lds_dwordx4 v177, s[16:17]
	s_nop 0
	s_mov_b32 m0, s36
	s_nop 0
	global_load_lds_dwordx4 v174, s[14:15]
	s_nop 0
	s_mov_b32 m0, s37
	s_nop 0
	global_load_lds_dwordx4 v176, s[14:15]
	s_waitcnt vmcnt(8)
	s_waitcnt lgkmcnt(0)
	s_barrier
	s_setprio 1
	s_waitcnt lgkmcnt(0)
	v_mfma_f32_16x16x32_bf16 v[64:67], v[112:115], v[164:167], v[64:67]
	v_mfma_f32_16x16x32_bf16 v[60:63], v[124:127], v[164:167], v[60:63]
	s_waitcnt lgkmcnt(5)
	v_mfma_f32_16x16x32_bf16 v[48:51], v[112:115], v[178:181], v[48:51]
	v_mfma_f32_16x16x32_bf16 v[44:47], v[124:127], v[178:181], v[44:47]
	s_waitcnt lgkmcnt(3)
	v_mfma_f32_16x16x32_bf16 v[32:35], v[112:115], v[196:199], v[32:35]
	v_mfma_f32_16x16x32_bf16 v[28:31], v[124:127], v[196:199], v[28:31]
	s_waitcnt lgkmcnt(1)
	v_mfma_f32_16x16x32_bf16 v[16:19], v[112:115], v[204:207], v[16:19]
	v_mfma_f32_16x16x32_bf16 v[12:15], v[124:127], v[204:207], v[12:15]
	v_mfma_f32_16x16x32_bf16 v[64:67], v[120:123], v[168:171], v[64:67]
	v_mfma_f32_16x16x32_bf16 v[60:63], v[132:135], v[168:171], v[60:63]
	v_mfma_f32_16x16x32_bf16 v[48:51], v[120:123], v[192:195], v[48:51]
	v_mfma_f32_16x16x32_bf16 v[44:47], v[132:135], v[192:195], v[44:47]
	v_mfma_f32_16x16x32_bf16 v[32:35], v[120:123], v[200:203], v[32:35]
	v_mfma_f32_16x16x32_bf16 v[28:31], v[132:135], v[200:203], v[28:31]
	s_waitcnt lgkmcnt(0)
	v_mfma_f32_16x16x32_bf16 v[16:19], v[120:123], v[208:211], v[16:19]
	v_mfma_f32_16x16x32_bf16 v[12:15], v[132:135], v[208:211], v[12:15]
	s_setprio 0
	s_setprio 1
	v_mfma_f32_16x16x32_bf16 v[56:59], v[148:151], v[164:167], v[56:59]
	v_mfma_f32_16x16x32_bf16 v[52:55], v[156:159], v[164:167], v[52:55]
	v_mfma_f32_16x16x32_bf16 v[40:43], v[148:151], v[178:181], v[40:43]
	v_mfma_f32_16x16x32_bf16 v[36:39], v[156:159], v[178:181], v[36:39]
	v_mfma_f32_16x16x32_bf16 v[24:27], v[148:151], v[196:199], v[24:27]
	v_mfma_f32_16x16x32_bf16 v[20:23], v[156:159], v[196:199], v[20:23]
	v_mfma_f32_16x16x32_bf16 v[6:9], v[148:151], v[204:207], v[8:11]
	v_mfma_f32_16x16x32_bf16 v[2:5], v[156:159], v[204:207], v[2:5]
	v_mfma_f32_16x16x32_bf16 v[56:59], v[152:155], v[168:171], v[56:59]
	v_mfma_f32_16x16x32_bf16 v[52:55], v[160:163], v[168:171], v[52:55]
	v_mfma_f32_16x16x32_bf16 v[40:43], v[152:155], v[192:195], v[40:43]
	v_mfma_f32_16x16x32_bf16 v[36:39], v[160:163], v[192:195], v[36:39]
	v_mfma_f32_16x16x32_bf16 v[24:27], v[152:155], v[200:203], v[24:27]
	v_mfma_f32_16x16x32_bf16 v[20:23], v[160:163], v[200:203], v[20:23]
	v_mfma_f32_16x16x32_bf16 v[8:11], v[152:155], v[208:211], v[6:9]
	v_mfma_f32_16x16x32_bf16 v[4:7], v[160:163], v[208:211], v[2:5]
	s_setprio 0
	s_barrier
	s_add_i32 s52, s52, 2
	s_add_u32 s53, s53, 0x100
	s_addc_u32 s57, s57, 0
	s_add_u32 s12, s12, 0x100
	s_addc_u32 s13, s13, 0
	s_cmpk_gt_u32 s52, 0x55
	s_cbranch_scc0 .LBB0_1226
	s_add_u32 s12, s8, 0x160080
	s_addc_u32 s13, s9, 0
	s_mov_b32 m0, s44
	s_nop 0
	global_load_lds_dwordx4 v174, s[12:13]
	v_lshl_add_u32 v2, s51, 8, v184
	s_mov_b32 m0, s45
	s_nop 0
	global_load_lds_dwordx4 v176, s[12:13]
	s_min_i32 s12, s51, 64
	s_ashr_i32 s12, s12, 4
	s_mul_hi_i32 s13, s12, 0xc000
	s_mul_i32 s12, s12, 0xc000
	v_ashrrev_i32_e32 v3, 31, v2
	v_lshl_or_b32 v148, s49, 8, v185
	s_add_u32 s12, s31, s12
	v_lshlrev_b64 v[2:3], 12, v[2:3]
	s_addc_u32 s13, s33, s13
	v_ashrrev_i32_e32 v149, 31, v148
	v_lshl_add_u64 v[2:3], s[80:81], 0, v[2:3]
	v_lshl_add_u64 v[112:113], v[148:149], 2, s[12:13]
	v_lshl_add_u64 v[2:3], v[148:149], 1, v[2:3]
	global_load_dwordx4 v[132:135], v[112:113], off
	global_load_dwordx4 v[124:127], v[112:113], off offset:16
	global_load_dwordx4 v[120:123], v[112:113], off offset:512
	global_load_dwordx4 v[112:115], v[112:113], off offset:528
	global_load_dwordx4 v[178:181], v[2:3], off
	global_load_dwordx4 v[192:195], v[2:3], off offset:256
	v_add_co_u32_e32 v172, vcc, 0x10000, v2
	s_nop 1
	v_addc_co_u32_e32 v173, vcc, 0, v3, vcc
	global_load_dwordx4 v[196:199], v[172:173], off
	global_load_dwordx4 v[164:167], v[172:173], off offset:256
	v_add_co_u32_e32 v170, vcc, 0x20000, v2
	s_nop 1
	v_addc_co_u32_e32 v171, vcc, 0, v3, vcc
	global_load_dwordx4 v[160:163], v[170:171], off
	global_load_dwordx4 v[156:159], v[170:171], off offset:256
	v_add_co_u32_e32 v168, vcc, 0x30000, v2
	s_nop 1
	v_addc_co_u32_e32 v169, vcc, 0, v3, vcc
	global_load_dwordx4 v[152:155], v[168:169], off
	global_load_dwordx4 v[148:151], v[168:169], off offset:256
	v_add_co_u32_e32 v244, vcc, 0x80000, v2
	s_nop 1
	v_addc_co_u32_e32 v245, vcc, 0, v3, vcc
	global_load_dwordx4 v[212:215], v[244:245], off
	global_load_dwordx4 v[216:219], v[244:245], off offset:256
	v_add_co_u32_e32 v246, vcc, 0x90000, v2
	s_nop 1
	v_addc_co_u32_e32 v247, vcc, 0, v3, vcc
	global_load_dwordx4 v[220:223], v[246:247], off
	global_load_dwordx4 v[224:227], v[246:247], off offset:256
	v_add_co_u32_e32 v248, vcc, 0xa0000, v2
	s_nop 1
	v_addc_co_u32_e32 v249, vcc, 0, v3, vcc
	global_load_dwordx4 v[228:231], v[248:249], off
	global_load_dwordx4 v[232:235], v[248:249], off offset:256
	v_add_co_u32_e32 v250, vcc, 0xb0000, v2
	s_nop 1
	v_addc_co_u32_e32 v251, vcc, 0, v3, vcc
	global_load_dwordx4 v[236:239], v[250:251], off
	global_load_dwordx4 v[240:243], v[250:251], off offset:256
	s_nop 0
	s_nop 0
	s_mov_b32 s12, 0x10000
	s_mov_b32 s12, 0x90000
	s_nop 0
	s_waitcnt vmcnt(15)
; __device__ __forceinline__ unsigned cvt_pk_bf16(float lo, float hi) { unsigned r; asm volatile("v_cvt_pk_bf16_f32 %0, %1, %2" : "=v"(r) : "v"(lo), "v"(hi)); return r; }
; #define ER_LOAD(dst, ai, mp) do { _Pragma("unroll") for (int mm = 0; mm < 2; ++mm) _Pragma("unroll") for (int bj = 0; bj < 2; ++bj) \
;             dst[mm][bj] = *(const u32x4*)(xb + (size_t)((ai) * HALF + (2 * (mp) + mm) * 16) * 2048 + bj * HALF); } while (0)
; __device__ __forceinline__ float x_lo(unsigned w) { if (XRES_F16) { const x_h2 h = __builtin_bit_cast(x_h2, w); return (float)h[0]; } return __builtin_bit_cast(float, w << 16); }
; __device__ __forceinline__ float x_hi(unsigned w) { if (XRES_F16) { const x_h2 h = __builtin_bit_cast(x_h2, w); return (float)h[1]; } return __builtin_bit_cast(float, w & 0xffff0000u); }
; __device__ __forceinline__ unsigned x_pk(float lo, float hi) { if (XRES_F16) { const x_f2 v = {lo, hi}; const x_h2 h = __builtin_convertvector(v, x_h2); return __builtin_bit_cast(unsigned, h); } return cvt_pk_bf16(lo, hi); }
; __device__ __forceinline__ u32x4 x_pack8(f32x4 v0, f32x4 v1) { u32x4 w; w.x = x_pk(v0[0], v0[1]); w.y = x_pk(v0[2], v0[3]); w.z = x_pk(v1[0], v1[1]); w.w = x_pk(v1[2], v1[3]); return w; }
;     __device__ __forceinline__ void operator()(const f32x4 (&acc)[2][2][4][2], const Unit& u, int wr, int wc, int fr, int fq) const {
;     ...
;         ER_LOAD(xa, 0, 0); ER_LOAD(xc, 0, 1);
;         ER_STORE(xa, 0, 0); ER_LOAD(xa, 1, 0);
;         ER_STORE(xc, 0, 1); ER_LOAD(xc, 1, 1);
;         ER_STORE(xa, 1, 0); ER_STORE(xc, 1, 1);
	v_cvt_f32_f16_e32 v200, v178
	v_cvt_f32_f16_sdwa v201, v178 dst_sel:DWORD dst_unused:UNUSED_PAD src0_sel:WORD_1
	s_nop 0
	v_cvt_f32_f16_e32 v178, v179
	v_cvt_f32_f16_sdwa v179, v179 dst_sel:DWORD dst_unused:UNUSED_PAD src0_sel:WORD_1
	v_fma_f32 v144, v144, v132, v200
	v_fma_f32 v145, v145, v133, v201
	v_fma_f32 v146, v146, v134, v178
	v_fma_f32 v147, v147, v135, v179
	v_cvt_f32_f16_e32 v178, v180
	v_cvt_f32_f16_sdwa v179, v180 dst_sel:DWORD dst_unused:UNUSED_PAD src0_sel:WORD_1
	v_cvt_f32_f16_e32 v180, v181
	v_cvt_f32_f16_sdwa v181, v181 dst_sel:DWORD dst_unused:UNUSED_PAD src0_sel:WORD_1
	v_fma_f32 v180, v142, v126, v180
	v_fma_f32 v181, v143, v127, v181
	v_fma_f32 v142, v140, v124, v178
	v_fma_f32 v143, v141, v125, v179
	v_cvt_pk_f16_f32 v140, v144, v145
	v_cvt_pk_f16_f32 v141, v146, v147
	v_cvt_pk_f16_f32 v142, v142, v143
	v_cvt_pk_f16_f32 v143, v180, v181
	global_store_dwordx4 v[2:3], v[140:143], off
	s_nop 1
	s_waitcnt vmcnt(15)
	v_cvt_f32_f16_e32 v140, v192
	v_cvt_f32_f16_sdwa v141, v192 dst_sel:DWORD dst_unused:UNUSED_PAD src0_sel:WORD_1
	v_cvt_f32_f16_e32 v142, v193
	v_cvt_f32_f16_sdwa v143, v193 dst_sel:DWORD dst_unused:UNUSED_PAD src0_sel:WORD_1
	v_fma_f32 v136, v136, v120, v140
	v_fma_f32 v137, v137, v121, v141
	v_cvt_f32_f16_e32 v140, v194
	v_fma_f32 v138, v138, v122, v142
	v_fma_f32 v139, v139, v123, v143
	v_cvt_f32_f16_sdwa v141, v194 dst_sel:DWORD dst_unused:UNUSED_PAD src0_sel:WORD_1
	v_cvt_f32_f16_e32 v142, v195
	v_cvt_f32_f16_sdwa v143, v195 dst_sel:DWORD dst_unused:UNUSED_PAD src0_sel:WORD_1
	v_fma_f32 v142, v130, v114, v142
	v_fma_f32 v143, v131, v115, v143
	v_fma_f32 v130, v128, v112, v140
	v_fma_f32 v131, v129, v113, v141
	v_cvt_pk_f16_f32 v128, v136, v137
	v_cvt_pk_f16_f32 v129, v138, v139
	v_cvt_pk_f16_f32 v130, v130, v131
	v_cvt_pk_f16_f32 v131, v142, v143
	global_store_dwordx4 v[2:3], v[128:131], off offset:256
	s_waitcnt vmcnt(13)
	v_cvt_f32_f16_e32 v136, v160
	v_cvt_f32_f16_e32 v128, v196
	v_cvt_f32_f16_sdwa v129, v196 dst_sel:DWORD dst_unused:UNUSED_PAD src0_sel:WORD_1
	v_cvt_f32_f16_e32 v130, v197
	v_cvt_f32_f16_sdwa v131, v197 dst_sel:DWORD dst_unused:UNUSED_PAD src0_sel:WORD_1
	v_cvt_f32_f16_sdwa v137, v160 dst_sel:DWORD dst_unused:UNUSED_PAD src0_sel:WORD_1
	v_fma_f32 v116, v116, v132, v128
	v_fma_f32 v117, v117, v133, v129
	v_cvt_f32_f16_e32 v128, v198
	v_fma_f32 v118, v118, v134, v130
	v_fma_f32 v119, v119, v135, v131
	v_cvt_f32_f16_sdwa v129, v198 dst_sel:DWORD dst_unused:UNUSED_PAD src0_sel:WORD_1
	v_cvt_f32_f16_e32 v130, v199
	v_cvt_f32_f16_sdwa v131, v199 dst_sel:DWORD dst_unused:UNUSED_PAD src0_sel:WORD_1
	v_cvt_f32_f16_e32 v138, v161
	v_cvt_f32_f16_sdwa v139, v161 dst_sel:DWORD dst_unused:UNUSED_PAD src0_sel:WORD_1
	v_fma_f32 v96, v96, v132, v136
	v_fma_f32 v97, v97, v133, v137
	v_fma_f32 v130, v110, v126, v130
	v_fma_f32 v131, v111, v127, v131
	v_fma_f32 v110, v108, v124, v128
	v_fma_f32 v111, v109, v125, v129
	v_cvt_pk_f16_f32 v108, v116, v117
	v_cvt_pk_f16_f32 v109, v118, v119
	v_cvt_pk_f16_f32 v110, v110, v111
	v_cvt_pk_f16_f32 v111, v130, v131
	global_store_dwordx4 v[172:173], v[108:111], off
	v_add_co_u32_e32 v130, vcc, s83, v2
	s_nop 0
	v_cvt_f32_f16_e32 v108, v164
	v_cvt_f32_f16_sdwa v109, v164 dst_sel:DWORD dst_unused:UNUSED_PAD src0_sel:WORD_1
	v_cvt_f32_f16_e32 v110, v165
	v_cvt_f32_f16_sdwa v111, v165 dst_sel:DWORD dst_unused:UNUSED_PAD src0_sel:WORD_1
	v_addc_co_u32_e32 v131, vcc, 0, v3, vcc
	v_fma_f32 v104, v104, v120, v108
	v_fma_f32 v105, v105, v121, v109
	v_fma_f32 v106, v106, v122, v110
	v_fma_f32 v107, v107, v123, v111
	v_cvt_f32_f16_e32 v108, v166
	v_cvt_f32_f16_sdwa v109, v166 dst_sel:DWORD dst_unused:UNUSED_PAD src0_sel:WORD_1
	v_cvt_f32_f16_e32 v110, v167
	v_cvt_f32_f16_sdwa v111, v167 dst_sel:DWORD dst_unused:UNUSED_PAD src0_sel:WORD_1
	v_fma_f32 v98, v98, v134, v138
	v_fma_f32 v99, v99, v135, v139
	v_cvt_f32_f16_e32 v136, v162
	v_cvt_f32_f16_sdwa v137, v162 dst_sel:DWORD dst_unused:UNUSED_PAD src0_sel:WORD_1
	v_fma_f32 v110, v102, v114, v110
	v_fma_f32 v111, v103, v115, v111
	v_fma_f32 v102, v100, v112, v108
	v_fma_f32 v103, v101, v113, v109
	v_cvt_pk_f16_f32 v100, v104, v105
	v_cvt_pk_f16_f32 v101, v106, v107
	v_cvt_pk_f16_f32 v102, v102, v103
	v_cvt_pk_f16_f32 v103, v110, v111
	global_store_dwordx4 v[172:173], v[100:103], off offset:256
	v_cvt_f32_f16_e32 v138, v163
	v_cvt_f32_f16_sdwa v139, v163 dst_sel:DWORD dst_unused:UNUSED_PAD src0_sel:WORD_1
	v_add_co_u32_e32 v128, vcc, s12, v2
	s_mov_b32 s12, 0xa0000
	v_fma_f32 v138, v94, v126, v138
	v_fma_f32 v139, v95, v127, v139
	v_fma_f32 v94, v92, v124, v136
	v_fma_f32 v95, v93, v125, v137
	v_addc_co_u32_e32 v129, vcc, 0, v3, vcc
	v_cvt_pk_f16_f32 v92, v96, v97
	v_cvt_pk_f16_f32 v93, v98, v99
	v_cvt_pk_f16_f32 v94, v94, v95
	v_cvt_pk_f16_f32 v95, v138, v139
	s_nop 0
	global_store_dwordx4 v[170:171], v[92:95], off
	s_nop 1
	s_waitcnt vmcnt(15)
	v_cvt_f32_f16_e32 v92, v156
	v_cvt_f32_f16_sdwa v93, v156 dst_sel:DWORD dst_unused:UNUSED_PAD src0_sel:WORD_1
	v_cvt_f32_f16_e32 v94, v157
	v_cvt_f32_f16_sdwa v95, v157 dst_sel:DWORD dst_unused:UNUSED_PAD src0_sel:WORD_1
	v_fma_f32 v88, v88, v120, v92
	v_fma_f32 v89, v89, v121, v93
	v_cvt_f32_f16_e32 v92, v158
	v_fma_f32 v90, v90, v122, v94
	v_fma_f32 v91, v91, v123, v95
	v_cvt_f32_f16_sdwa v93, v158 dst_sel:DWORD dst_unused:UNUSED_PAD src0_sel:WORD_1
	v_cvt_f32_f16_e32 v94, v159
	v_cvt_f32_f16_sdwa v95, v159 dst_sel:DWORD dst_unused:UNUSED_PAD src0_sel:WORD_1
	v_fma_f32 v94, v86, v114, v94
	v_fma_f32 v95, v87, v115, v95
	v_fma_f32 v86, v84, v112, v92
	v_fma_f32 v87, v85, v113, v93
	v_cvt_pk_f16_f32 v84, v88, v89
	v_cvt_pk_f16_f32 v85, v90, v91
	v_cvt_pk_f16_f32 v86, v86, v87
	v_cvt_pk_f16_f32 v87, v94, v95
	global_store_dwordx4 v[170:171], v[84:87], off offset:256
	s_waitcnt vmcnt(13)
; __device__ __forceinline__ unsigned cvt_pk_bf16(float lo, float hi) { unsigned r; asm volatile("v_cvt_pk_bf16_f32 %0, %1, %2" : "=v"(r) : "v"(lo), "v"(hi)); return r; }
; #define ER_LOAD(dst, ai, mp) do { _Pragma("unroll") for (int mm = 0; mm < 2; ++mm) _Pragma("unroll") for (int bj = 0; bj < 2; ++bj) \
;             dst[mm][bj] = *(const u32x4*)(xb + (size_t)((ai) * HALF + (2 * (mp) + mm) * 16) * 2048 + bj * HALF); } while (0)
; __device__ __forceinline__ float x_lo(unsigned w) { if (XRES_F16) { const x_h2 h = __builtin_bit_cast(x_h2, w); return (float)h[0]; } return __builtin_bit_cast(float, w << 16); }
; __device__ __forceinline__ float x_hi(unsigned w) { if (XRES_F16) { const x_h2 h = __builtin_bit_cast(x_h2, w); return (float)h[1]; } return __builtin_bit_cast(float, w & 0xffff0000u); }
; __device__ __forceinline__ unsigned x_pk(float lo, float hi) { if (XRES_F16) { const x_f2 v = {lo, hi}; const x_h2 h = __builtin_convertvector(v, x_h2); return __builtin_bit_cast(unsigned, h); } return cvt_pk_bf16(lo, hi); }
; __device__ __forceinline__ u32x4 x_pack8(f32x4 v0, f32x4 v1) { u32x4 w; w.x = x_pk(v0[0], v0[1]); w.y = x_pk(v0[2], v0[3]); w.z = x_pk(v1[0], v1[1]); w.w = x_pk(v1[2], v1[3]); return w; }
;     __device__ __forceinline__ void operator()(const f32x4 (&acc)[2][2][4][2], const Unit& u, int wr, int wc, int fr, int fq) const {
;     ...
;         ER_LOAD(xa, 0, 0); ER_LOAD(xc, 0, 1);
;         ER_STORE(xa, 0, 0); ER_LOAD(xa, 1, 0);
;         ER_STORE(xc, 0, 1); ER_LOAD(xc, 1, 1);
;         ER_STORE(xa, 1, 0); ER_STORE(xc, 1, 1);
	v_cvt_f32_f16_e32 v88, v213
	v_cvt_f32_f16_e32 v84, v152
	v_cvt_f32_f16_sdwa v85, v152 dst_sel:DWORD dst_unused:UNUSED_PAD src0_sel:WORD_1
	v_cvt_f32_f16_e32 v86, v153
	v_cvt_f32_f16_sdwa v87, v153 dst_sel:DWORD dst_unused:UNUSED_PAD src0_sel:WORD_1
	v_cvt_f32_f16_sdwa v89, v213 dst_sel:DWORD dst_unused:UNUSED_PAD src0_sel:WORD_1
	v_fma_f32 v80, v80, v132, v84
	v_fma_f32 v81, v81, v133, v85
	v_cvt_f32_f16_e32 v84, v154
	v_fma_f32 v82, v82, v134, v86
	v_fma_f32 v83, v83, v135, v87
	v_cvt_f32_f16_sdwa v85, v154 dst_sel:DWORD dst_unused:UNUSED_PAD src0_sel:WORD_1
	v_cvt_f32_f16_e32 v86, v155
	v_cvt_f32_f16_sdwa v87, v155 dst_sel:DWORD dst_unused:UNUSED_PAD src0_sel:WORD_1
	v_fma_f32 v66, v66, v134, v88
	v_fma_f32 v67, v67, v135, v89
	v_cvt_f32_f16_e32 v88, v215
	v_cvt_f32_f16_sdwa v89, v215 dst_sel:DWORD dst_unused:UNUSED_PAD src0_sel:WORD_1
	v_fma_f32 v86, v78, v126, v86
	v_fma_f32 v87, v79, v127, v87
	v_fma_f32 v78, v76, v124, v84
	v_fma_f32 v79, v77, v125, v85
	v_cvt_pk_f16_f32 v76, v80, v81
	v_cvt_pk_f16_f32 v77, v82, v83
	v_cvt_pk_f16_f32 v78, v78, v79
	v_cvt_pk_f16_f32 v79, v86, v87
	global_store_dwordx4 v[168:169], v[76:79], off
	v_add_co_u32_e32 v84, vcc, s12, v2
	s_nop 0
	v_cvt_f32_f16_e32 v76, v148
	v_cvt_f32_f16_sdwa v77, v148 dst_sel:DWORD dst_unused:UNUSED_PAD src0_sel:WORD_1
	v_cvt_f32_f16_e32 v78, v149
	v_cvt_f32_f16_sdwa v79, v149 dst_sel:DWORD dst_unused:UNUSED_PAD src0_sel:WORD_1
	v_addc_co_u32_e32 v85, vcc, 0, v3, vcc
	v_fma_f32 v72, v72, v120, v76
	v_fma_f32 v73, v73, v121, v77
	v_fma_f32 v74, v74, v122, v78
	v_fma_f32 v75, v75, v123, v79
	v_cvt_f32_f16_e32 v76, v150
	v_cvt_f32_f16_sdwa v77, v150 dst_sel:DWORD dst_unused:UNUSED_PAD src0_sel:WORD_1
	v_cvt_f32_f16_e32 v78, v151
	v_cvt_f32_f16_sdwa v79, v151 dst_sel:DWORD dst_unused:UNUSED_PAD src0_sel:WORD_1
	s_mov_b32 s12, 0xb0000
	v_add_co_u32_e32 v2, vcc, s12, v2
	v_fma_f32 v78, v70, v114, v78
	v_fma_f32 v79, v71, v115, v79
	v_fma_f32 v70, v68, v112, v76
	v_fma_f32 v71, v69, v113, v77
	v_cvt_pk_f16_f32 v68, v72, v73
	v_cvt_pk_f16_f32 v69, v74, v75
	v_cvt_pk_f16_f32 v70, v70, v71
	v_cvt_pk_f16_f32 v71, v78, v79
	global_store_dwordx4 v[168:169], v[68:71], off offset:256
	v_addc_co_u32_e32 v3, vcc, 0, v3, vcc
	v_cvt_f32_f16_e32 v86, v212
	v_cvt_f32_f16_sdwa v87, v212 dst_sel:DWORD dst_unused:UNUSED_PAD src0_sel:WORD_1
	v_fma_f32 v88, v62, v126, v88
	v_fma_f32 v89, v63, v127, v89
	s_mov_b64 s[12:13], -1
	s_and_b64 vcc, exec, s[10:11]
	v_fma_f32 v64, v64, v132, v86
	v_fma_f32 v65, v65, v133, v87
	v_cvt_f32_f16_e32 v86, v214
	v_cvt_f32_f16_sdwa v87, v214 dst_sel:DWORD dst_unused:UNUSED_PAD src0_sel:WORD_1
	v_fma_f32 v62, v60, v124, v86
	v_fma_f32 v63, v61, v125, v87
	v_cvt_pk_f16_f32 v60, v64, v65
	v_cvt_pk_f16_f32 v61, v66, v67
	v_cvt_pk_f16_f32 v62, v62, v63
	v_cvt_pk_f16_f32 v63, v88, v89
	global_store_dwordx4 v[130:131], v[60:63], off
	s_nop 1
	s_waitcnt vmcnt(15)
	v_cvt_f32_f16_e32 v60, v216
	v_cvt_f32_f16_sdwa v61, v216 dst_sel:DWORD dst_unused:UNUSED_PAD src0_sel:WORD_1
	v_cvt_f32_f16_e32 v62, v217
	v_cvt_f32_f16_sdwa v63, v217 dst_sel:DWORD dst_unused:UNUSED_PAD src0_sel:WORD_1
	v_fma_f32 v56, v56, v120, v60
	v_fma_f32 v57, v57, v121, v61
	v_cvt_f32_f16_e32 v60, v218
	v_fma_f32 v58, v58, v122, v62
	v_fma_f32 v59, v59, v123, v63
	v_cvt_f32_f16_sdwa v61, v218 dst_sel:DWORD dst_unused:UNUSED_PAD src0_sel:WORD_1
	v_cvt_f32_f16_e32 v62, v219
	v_cvt_f32_f16_sdwa v63, v219 dst_sel:DWORD dst_unused:UNUSED_PAD src0_sel:WORD_1
	v_fma_f32 v62, v54, v114, v62
	v_fma_f32 v63, v55, v115, v63
	v_fma_f32 v54, v52, v112, v60
	v_fma_f32 v55, v53, v113, v61
	v_cvt_pk_f16_f32 v52, v56, v57
	v_cvt_pk_f16_f32 v53, v58, v59
	v_cvt_pk_f16_f32 v54, v54, v55
	v_cvt_pk_f16_f32 v55, v62, v63
	global_store_dwordx4 v[130:131], v[52:55], off offset:256
	s_nop 1
	s_waitcnt vmcnt(15)
	v_cvt_f32_f16_e32 v52, v220
	v_cvt_f32_f16_sdwa v53, v220 dst_sel:DWORD dst_unused:UNUSED_PAD src0_sel:WORD_1
	v_cvt_f32_f16_e32 v54, v221
	v_cvt_f32_f16_sdwa v55, v221 dst_sel:DWORD dst_unused:UNUSED_PAD src0_sel:WORD_1
	v_fma_f32 v48, v48, v132, v52
	v_fma_f32 v49, v49, v133, v53
	v_cvt_f32_f16_e32 v52, v222
	v_fma_f32 v50, v50, v134, v54
	v_fma_f32 v51, v51, v135, v55
	v_cvt_f32_f16_sdwa v53, v222 dst_sel:DWORD dst_unused:UNUSED_PAD src0_sel:WORD_1
	v_cvt_f32_f16_e32 v54, v223
	v_cvt_f32_f16_sdwa v55, v223 dst_sel:DWORD dst_unused:UNUSED_PAD src0_sel:WORD_1
	v_fma_f32 v54, v46, v126, v54
	v_fma_f32 v55, v47, v127, v55
	v_fma_f32 v46, v44, v124, v52
	v_fma_f32 v47, v45, v125, v53
	v_cvt_pk_f16_f32 v44, v48, v49
	v_cvt_pk_f16_f32 v45, v50, v51
	v_cvt_pk_f16_f32 v46, v46, v47
	v_cvt_pk_f16_f32 v47, v54, v55
	global_store_dwordx4 v[128:129], v[44:47], off
	s_nop 1
	s_waitcnt vmcnt(15)
	v_cvt_f32_f16_e32 v44, v224
	v_cvt_f32_f16_sdwa v45, v224 dst_sel:DWORD dst_unused:UNUSED_PAD src0_sel:WORD_1
	v_cvt_f32_f16_e32 v46, v225
	v_cvt_f32_f16_sdwa v47, v225 dst_sel:DWORD dst_unused:UNUSED_PAD src0_sel:WORD_1
	v_fma_f32 v40, v40, v120, v44
	v_fma_f32 v41, v41, v121, v45
	v_cvt_f32_f16_e32 v44, v226
	v_fma_f32 v42, v42, v122, v46
	v_fma_f32 v43, v43, v123, v47
	v_cvt_f32_f16_sdwa v45, v226 dst_sel:DWORD dst_unused:UNUSED_PAD src0_sel:WORD_1
	v_cvt_f32_f16_e32 v46, v227
	v_cvt_f32_f16_sdwa v47, v227 dst_sel:DWORD dst_unused:UNUSED_PAD src0_sel:WORD_1
	v_fma_f32 v46, v38, v114, v46
	v_fma_f32 v47, v39, v115, v47
	v_fma_f32 v38, v36, v112, v44
	v_fma_f32 v39, v37, v113, v45
	v_cvt_pk_f16_f32 v36, v40, v41
	v_cvt_pk_f16_f32 v37, v42, v43
	v_cvt_pk_f16_f32 v38, v38, v39
	v_cvt_pk_f16_f32 v39, v46, v47
	global_store_dwordx4 v[128:129], v[36:39], off offset:256
	s_nop 0
	s_waitcnt vmcnt(15)
; #define ER_LOAD(dst, ai, mp) do { _Pragma("unroll") for (int mm = 0; mm < 2; ++mm) _Pragma("unroll") for (int bj = 0; bj < 2; ++bj) \
;             dst[mm][bj] = *(const u32x4*)(xb + (size_t)((ai) * HALF + (2 * (mp) + mm) * 16) * 2048 + bj * HALF); } while (0)
;     __device__ __forceinline__ void operator()(const f32x4 (&acc)[2][2][4][2], const Unit& u, int wr, int wc, int fr, int fq) const {
;     ...
;         ER_LOAD(xa, 0, 0); ER_LOAD(xc, 0, 1);
;         ER_STORE(xa, 0, 0); ER_LOAD(xa, 1, 0);
;         ER_STORE(xc, 0, 1); ER_LOAD(xc, 1, 1);
;         ER_STORE(xa, 1, 0); ER_STORE(xc, 1, 1);
	v_cvt_f32_f16_e32 v36, v228
	v_cvt_f32_f16_sdwa v37, v228 dst_sel:DWORD dst_unused:UNUSED_PAD src0_sel:WORD_1
	v_cvt_f32_f16_e32 v38, v229
	v_cvt_f32_f16_sdwa v39, v229 dst_sel:DWORD dst_unused:UNUSED_PAD src0_sel:WORD_1
	v_fma_f32 v32, v32, v132, v36
	v_fma_f32 v33, v33, v133, v37
	v_cvt_f32_f16_e32 v36, v230
	v_fma_f32 v34, v34, v134, v38
	v_fma_f32 v35, v35, v135, v39
	v_cvt_f32_f16_sdwa v37, v230 dst_sel:DWORD dst_unused:UNUSED_PAD src0_sel:WORD_1
	v_cvt_f32_f16_e32 v38, v231
	v_cvt_f32_f16_sdwa v39, v231 dst_sel:DWORD dst_unused:UNUSED_PAD src0_sel:WORD_1
	v_fma_f32 v38, v30, v126, v38
	v_fma_f32 v39, v31, v127, v39
	v_fma_f32 v30, v28, v124, v36
	v_fma_f32 v31, v29, v125, v37
	v_cvt_pk_f16_f32 v28, v32, v33
	v_cvt_pk_f16_f32 v29, v34, v35
	v_cvt_pk_f16_f32 v30, v30, v31
	v_cvt_pk_f16_f32 v31, v38, v39
	global_store_dwordx4 v[84:85], v[28:31], off
	s_nop 1
	s_waitcnt vmcnt(15)
	v_cvt_f32_f16_e32 v28, v232
	v_cvt_f32_f16_sdwa v29, v232 dst_sel:DWORD dst_unused:UNUSED_PAD src0_sel:WORD_1
	v_cvt_f32_f16_e32 v30, v233
	v_cvt_f32_f16_sdwa v31, v233 dst_sel:DWORD dst_unused:UNUSED_PAD src0_sel:WORD_1
	v_fma_f32 v24, v24, v120, v28
	v_fma_f32 v25, v25, v121, v29
	v_cvt_f32_f16_e32 v28, v234
	v_fma_f32 v26, v26, v122, v30
	v_fma_f32 v27, v27, v123, v31
	v_cvt_f32_f16_sdwa v29, v234 dst_sel:DWORD dst_unused:UNUSED_PAD src0_sel:WORD_1
	v_cvt_f32_f16_e32 v30, v235
	v_cvt_f32_f16_sdwa v31, v235 dst_sel:DWORD dst_unused:UNUSED_PAD src0_sel:WORD_1
	v_fma_f32 v30, v22, v114, v30
	v_fma_f32 v31, v23, v115, v31
	v_fma_f32 v22, v20, v112, v28
	v_fma_f32 v23, v21, v113, v29
	v_cvt_pk_f16_f32 v20, v24, v25
	v_cvt_pk_f16_f32 v21, v26, v27
	v_cvt_pk_f16_f32 v22, v22, v23
	v_cvt_pk_f16_f32 v23, v30, v31
	global_store_dwordx4 v[84:85], v[20:23], off offset:256
	s_nop 1
	s_waitcnt vmcnt(15)
	v_cvt_f32_f16_e32 v20, v236
	v_cvt_f32_f16_sdwa v21, v236 dst_sel:DWORD dst_unused:UNUSED_PAD src0_sel:WORD_1
	v_cvt_f32_f16_e32 v22, v237
	v_cvt_f32_f16_sdwa v23, v237 dst_sel:DWORD dst_unused:UNUSED_PAD src0_sel:WORD_1
	v_fma_f32 v16, v16, v132, v20
	v_fma_f32 v17, v17, v133, v21
	v_cvt_f32_f16_e32 v20, v238
	v_fma_f32 v18, v18, v134, v22
	v_fma_f32 v19, v19, v135, v23
	v_cvt_f32_f16_sdwa v21, v238 dst_sel:DWORD dst_unused:UNUSED_PAD src0_sel:WORD_1
	v_cvt_f32_f16_e32 v22, v239
	v_cvt_f32_f16_sdwa v23, v239 dst_sel:DWORD dst_unused:UNUSED_PAD src0_sel:WORD_1
	v_fma_f32 v22, v14, v126, v22
	v_fma_f32 v23, v15, v127, v23
	v_fma_f32 v14, v12, v124, v20
	v_fma_f32 v15, v13, v125, v21
	v_cvt_pk_f16_f32 v12, v16, v17
	v_cvt_pk_f16_f32 v13, v18, v19
	v_cvt_pk_f16_f32 v14, v14, v15
	v_cvt_pk_f16_f32 v15, v22, v23
	global_store_dwordx4 v[2:3], v[12:15], off
	s_nop 1
	s_waitcnt vmcnt(15)
	v_cvt_f32_f16_e32 v12, v240
	v_cvt_f32_f16_sdwa v13, v240 dst_sel:DWORD dst_unused:UNUSED_PAD src0_sel:WORD_1
	v_cvt_f32_f16_e32 v14, v241
	v_cvt_f32_f16_sdwa v15, v241 dst_sel:DWORD dst_unused:UNUSED_PAD src0_sel:WORD_1
	v_fma_f32 v8, v8, v120, v12
	v_fma_f32 v9, v9, v121, v13
	v_cvt_f32_f16_e32 v12, v242
	v_fma_f32 v10, v10, v122, v14
	v_fma_f32 v11, v11, v123, v15
	v_cvt_f32_f16_sdwa v13, v242 dst_sel:DWORD dst_unused:UNUSED_PAD src0_sel:WORD_1
	v_cvt_f32_f16_e32 v14, v243
	v_cvt_f32_f16_sdwa v15, v243 dst_sel:DWORD dst_unused:UNUSED_PAD src0_sel:WORD_1
	v_fma_f32 v14, v6, v114, v14
	v_fma_f32 v15, v7, v115, v15
	v_fma_f32 v6, v4, v112, v12
	v_fma_f32 v7, v5, v113, v13
	v_cvt_pk_f16_f32 v4, v8, v9
	v_cvt_pk_f16_f32 v5, v10, v11
	v_cvt_pk_f16_f32 v6, v6, v7
	v_cvt_pk_f16_f32 v7, v14, v15
	global_store_dwordx4 v[2:3], v[4:7], off offset:256
	s_cbranch_vccz .LBB0_1209
	ds_read_b128 v[2:5], v0
	ds_read_b128 v[6:9], v0 offset:1024
	ds_read_b128 v[10:13], v0 offset:2048
	ds_read_b128 v[14:17], v0 offset:3072
	ds_read_b128 v[18:21], v188
	ds_read_b128 v[22:25], v188 offset:1024
	ds_read_b128 v[26:29], v188 offset:2048
	ds_read_b128 v[30:33], v188 offset:3072
	s_add_u32 s12, s8, 0x100
	s_addc_u32 s13, s9, 0
	s_add_u32 s10, s8, 0x180
	s_addc_u32 s11, s9, 0
	s_add_u32 s14, s6, 0x100
	s_addc_u32 s15, s7, 0
	ds_read_b128 v[34:37], v187
	ds_read_b128 v[38:41], v187 offset:1024
	ds_read_b128 v[42:45], v187 offset:2048
	ds_read_b128 v[46:49], v187 offset:3072
	ds_read_b128 v[50:53], v187 offset:4096
	ds_read_b128 v[54:57], v187 offset:5120
	ds_read_b128 v[58:61], v187 offset:6144
	ds_read_b128 v[62:65], v187 offset:7168
	s_waitcnt vmcnt(44)
	s_waitcnt lgkmcnt(0)
	s_barrier
	s_setprio 1
	s_waitcnt lgkmcnt(0)
	v_mfma_f32_16x16x32_bf16 v[90:93], v[2:5], v[58:61], 0
	v_mfma_f32_16x16x32_bf16 v[66:69], v[2:5], v[34:37], 0
	v_mfma_f32_16x16x32_bf16 v[70:73], v[10:13], v[34:37], 0
	v_mfma_f32_16x16x32_bf16 v[74:77], v[2:5], v[42:45], 0
	v_mfma_f32_16x16x32_bf16 v[78:81], v[10:13], v[42:45], 0
	v_mfma_f32_16x16x32_bf16 v[82:85], v[2:5], v[50:53], 0
	v_mfma_f32_16x16x32_bf16 v[86:89], v[10:13], v[50:53], 0
	v_mfma_f32_16x16x32_bf16 v[100:103], v[6:9], v[62:65], v[90:93]
	v_mfma_f32_16x16x32_bf16 v[90:93], v[10:13], v[58:61], 0
	v_mfma_f32_16x16x32_bf16 v[66:69], v[6:9], v[38:41], v[66:69]
	v_mfma_f32_16x16x32_bf16 v[70:73], v[14:17], v[38:41], v[70:73]
	v_mfma_f32_16x16x32_bf16 v[74:77], v[6:9], v[46:49], v[74:77]
	v_mfma_f32_16x16x32_bf16 v[78:81], v[14:17], v[46:49], v[78:81]
	v_mfma_f32_16x16x32_bf16 v[82:85], v[6:9], v[54:57], v[82:85]
	v_mfma_f32_16x16x32_bf16 v[86:89], v[14:17], v[54:57], v[86:89]
	v_mfma_f32_16x16x32_bf16 v[104:107], v[14:17], v[62:65], v[90:93]
	s_setprio 0
	s_setprio 1
	v_mfma_f32_16x16x32_bf16 v[90:93], v[18:21], v[34:37], 0
	v_mfma_f32_16x16x32_bf16 v[34:37], v[26:29], v[34:37], 0
	v_mfma_f32_16x16x32_bf16 v[112:115], v[22:25], v[38:41], v[90:93]
	v_mfma_f32_16x16x32_bf16 v[34:37], v[30:33], v[38:41], v[34:37]
	v_mfma_f32_16x16x32_bf16 v[38:41], v[18:21], v[42:45], 0
	v_mfma_f32_16x16x32_bf16 v[42:45], v[26:29], v[42:45], 0
	v_mfma_f32_16x16x32_bf16 v[38:41], v[22:25], v[46:49], v[38:41]
	v_mfma_f32_16x16x32_bf16 v[42:45], v[30:33], v[46:49], v[42:45]
	v_mfma_f32_16x16x32_bf16 v[46:49], v[18:21], v[50:53], 0
	v_mfma_f32_16x16x32_bf16 v[50:53], v[26:29], v[50:53], 0
	v_mfma_f32_16x16x32_bf16 v[46:49], v[22:25], v[54:57], v[46:49]
	v_mfma_f32_16x16x32_bf16 v[50:53], v[30:33], v[54:57], v[50:53]
	v_mfma_f32_16x16x32_bf16 v[54:57], v[18:21], v[58:61], 0
	v_mfma_f32_16x16x32_bf16 v[58:61], v[26:29], v[58:61], 0
	v_mfma_f32_16x16x32_bf16 v[54:57], v[22:25], v[62:65], v[54:57]
	v_mfma_f32_16x16x32_bf16 v[58:61], v[30:33], v[62:65], v[58:61]
	s_setprio 0
	s_barrier
	ds_read_b128 v[62:65], v187 offset:16384
	ds_read_b128 v[90:93], v187 offset:17408
	ds_read_b128 v[94:97], v187 offset:18432
	ds_read_b128 v[108:111], v187 offset:19456
	ds_read_b128 v[116:119], v187 offset:20480
	ds_read_b128 v[120:123], v187 offset:21504
	ds_read_b128 v[124:127], v187 offset:22528
	ds_read_b128 v[128:131], v187 offset:23552
	s_mov_b32 m0, s22
	s_nop 0
	global_load_lds_dwordx4 v175, s[14:15]
	s_nop 0
	s_mov_b32 m0, s23
	s_nop 0
	global_load_lds_dwordx4 v177, s[14:15]
	s_add_u32 s14, s6, 0x160100
	s_addc_u32 s15, s7, 0
	s_mov_b32 m0, s26
	s_nop 0
	global_load_lds_dwordx4 v175, s[14:15]
	s_nop 0
	s_mov_b32 m0, s27
	s_nop 0
	global_load_lds_dwordx4 v177, s[14:15]
	s_nop 0
	s_mov_b32 m0, s21
	s_nop 0
	global_load_lds_dwordx4 v174, s[12:13]
	s_nop 0
	s_mov_b32 m0, s28
	s_nop 0
	global_load_lds_dwordx4 v176, s[12:13]
	s_waitcnt vmcnt(44)
	s_waitcnt lgkmcnt(0)
	s_barrier
	s_setprio 1
	s_waitcnt lgkmcnt(0)
	v_mfma_f32_16x16x32_bf16 v[136:139], v[10:13], v[62:65], 0
	v_mfma_f32_16x16x32_bf16 v[148:151], v[14:17], v[90:93], v[136:139]
	v_mfma_f32_16x16x32_bf16 v[136:139], v[2:5], v[94:97], 0
	v_mfma_f32_16x16x32_bf16 v[152:155], v[6:9], v[108:111], v[136:139]
	v_mfma_f32_16x16x32_bf16 v[136:139], v[10:13], v[94:97], 0
	v_mfma_f32_16x16x32_bf16 v[132:135], v[2:5], v[62:65], 0
	v_mfma_f32_16x16x32_bf16 v[156:159], v[14:17], v[108:111], v[136:139]
	v_mfma_f32_16x16x32_bf16 v[136:139], v[2:5], v[116:119], 0
	v_mfma_f32_16x16x32_bf16 v[2:5], v[2:5], v[124:127], 0
	v_mfma_f32_16x16x32_bf16 v[132:135], v[6:9], v[90:93], v[132:135]
	v_mfma_f32_16x16x32_bf16 v[160:163], v[6:9], v[120:123], v[136:139]
	v_mfma_f32_16x16x32_bf16 v[2:5], v[6:9], v[128:131], v[2:5]
	v_mfma_f32_16x16x32_bf16 v[6:9], v[10:13], v[124:127], 0
	v_mfma_f32_16x16x32_bf16 v[136:139], v[10:13], v[116:119], 0
	v_mfma_f32_16x16x32_bf16 v[6:9], v[14:17], v[128:131], v[6:9]
	v_mfma_f32_16x16x32_bf16 v[164:167], v[14:17], v[120:123], v[136:139]
	s_setprio 0
	s_setprio 1
	v_mfma_f32_16x16x32_bf16 v[10:13], v[18:21], v[62:65], 0
	v_mfma_f32_16x16x32_bf16 v[168:171], v[22:25], v[90:93], v[10:13]
	v_mfma_f32_16x16x32_bf16 v[10:13], v[26:29], v[62:65], 0
	v_mfma_f32_16x16x32_bf16 v[178:181], v[30:33], v[90:93], v[10:13]
	v_mfma_f32_16x16x32_bf16 v[10:13], v[18:21], v[94:97], 0
	v_mfma_f32_16x16x32_bf16 v[192:195], v[22:25], v[108:111], v[10:13]
	v_mfma_f32_16x16x32_bf16 v[10:13], v[26:29], v[94:97], 0
	v_mfma_f32_16x16x32_bf16 v[196:199], v[30:33], v[108:111], v[10:13]
	v_mfma_f32_16x16x32_bf16 v[10:13], v[18:21], v[116:119], 0
	v_mfma_f32_16x16x32_bf16 v[200:203], v[22:25], v[120:123], v[10:13]
	v_mfma_f32_16x16x32_bf16 v[10:13], v[26:29], v[116:119], 0
	v_mfma_f32_16x16x32_bf16 v[120:123], v[30:33], v[120:123], v[10:13]
	v_mfma_f32_16x16x32_bf16 v[10:13], v[18:21], v[124:127], 0
	v_mfma_f32_16x16x32_bf16 v[204:207], v[22:25], v[128:131], v[10:13]
	v_mfma_f32_16x16x32_bf16 v[10:13], v[26:29], v[124:127], 0
	v_mfma_f32_16x16x32_bf16 v[124:127], v[30:33], v[128:131], v[10:13]
	s_setprio 0
	s_barrier
	s_nop 4
	ds_read_b128 v[10:13], v189
	ds_read_b128 v[14:17], v189 offset:1024
	ds_read_b128 v[20:23], v189 offset:2048
	ds_read_b128 v[24:27], v189 offset:3072
	ds_read_b128 v[208:211], v190
	ds_read_b128 v[212:215], v190 offset:1024
	ds_read_b128 v[216:219], v190 offset:2048
	ds_read_b128 v[188:191], v190 offset:3072
	ds_read_b128 v[28:31], v187 offset:32768
	ds_read_b128 v[62:65], v187 offset:33792
	ds_read_b128 v[220:223], v187 offset:34816
	ds_read_b128 v[224:227], v187 offset:35840
	ds_read_b128 v[228:231], v187 offset:36864
	ds_read_b128 v[232:235], v187 offset:37888
	ds_read_b128 v[236:239], v187 offset:38912
	ds_read_b128 v[240:243], v187 offset:39936
	s_add_u32 s12, s8, 0x160100
	s_addc_u32 s13, s9, 0
	s_mov_b32 m0, s29
	s_nop 0
	global_load_lds_dwordx4 v174, s[12:13]
	s_nop 0
	s_mov_b32 m0, s30
	s_nop 0
	global_load_lds_dwordx4 v176, s[12:13]
	s_waitcnt vmcnt(44)
	s_waitcnt lgkmcnt(0)
	s_barrier
; template <class Epi, class Sched, bool ALIGN_EPI = false, bool SP2 = false>
; __device__ __forceinline__ void gemm_phase(PG8_LAS unsigned char* lds, const Gemm g, const Sched& S, const Epi& E) {
;     ...
;         if constexpr (DRO) {
;             const char* a1 = cA + kstep; const char* a2 = cA + 2 * kstep; const char* b2 = cB + 2 * kstep; const char* a3 = a2 + kstep; const char* b3 = b2 + kstep;
;             PG8_TRIP(false, asm volatile("s_waitcnt vmcnt(%0)" :: "n"(8 + Epi::NVM) : "memory"));
;         }
	s_setprio 1
	s_waitcnt lgkmcnt(0)
	v_mfma_f32_16x16x32_bf16 v[66:69], v[10:13], v[28:31], v[66:69]
	v_mfma_f32_16x16x32_bf16 v[144:147], v[14:17], v[62:65], v[66:69]
	v_mfma_f32_16x16x32_bf16 v[66:69], v[20:23], v[28:31], v[70:73]
	v_mfma_f32_16x16x32_bf16 v[140:143], v[24:27], v[62:65], v[66:69]
	v_mfma_f32_16x16x32_bf16 v[66:69], v[10:13], v[220:223], v[74:77]
	v_mfma_f32_16x16x32_bf16 v[116:119], v[14:17], v[224:227], v[66:69]
	v_mfma_f32_16x16x32_bf16 v[66:69], v[20:23], v[220:223], v[78:81]
	v_mfma_f32_16x16x32_bf16 v[108:111], v[24:27], v[224:227], v[66:69]
	v_mfma_f32_16x16x32_bf16 v[66:69], v[10:13], v[228:231], v[82:85]
	v_mfma_f32_16x16x32_bf16 v[96:99], v[14:17], v[232:235], v[66:69]
	v_mfma_f32_16x16x32_bf16 v[66:69], v[20:23], v[228:231], v[86:89]
	v_mfma_f32_16x16x32_bf16 v[92:95], v[24:27], v[232:235], v[66:69]
	v_mfma_f32_16x16x32_bf16 v[66:69], v[10:13], v[236:239], v[100:103]
	v_mfma_f32_16x16x32_bf16 v[80:83], v[14:17], v[240:243], v[66:69]
	v_mfma_f32_16x16x32_bf16 v[66:69], v[20:23], v[236:239], v[104:107]
	v_mfma_f32_16x16x32_bf16 v[76:79], v[24:27], v[240:243], v[66:69]
	s_setprio 0
	s_setprio 1
	v_mfma_f32_16x16x32_bf16 v[66:69], v[208:211], v[28:31], v[112:115]
	v_mfma_f32_16x16x32_bf16 v[28:31], v[216:219], v[28:31], v[34:37]
	v_mfma_f32_16x16x32_bf16 v[128:131], v[188:191], v[62:65], v[28:31]
	v_mfma_f32_16x16x32_bf16 v[28:31], v[208:211], v[220:223], v[38:41]
	v_mfma_f32_16x16x32_bf16 v[104:107], v[212:215], v[224:227], v[28:31]
	v_mfma_f32_16x16x32_bf16 v[28:31], v[216:219], v[220:223], v[42:45]
	v_mfma_f32_16x16x32_bf16 v[100:103], v[188:191], v[224:227], v[28:31]
	v_mfma_f32_16x16x32_bf16 v[28:31], v[208:211], v[228:231], v[46:49]
	v_mfma_f32_16x16x32_bf16 v[88:91], v[212:215], v[232:235], v[28:31]
	v_mfma_f32_16x16x32_bf16 v[28:31], v[216:219], v[228:231], v[50:53]
	v_mfma_f32_16x16x32_bf16 v[84:87], v[188:191], v[232:235], v[28:31]
	v_mfma_f32_16x16x32_bf16 v[28:31], v[208:211], v[236:239], v[54:57]
	v_mfma_f32_16x16x32_bf16 v[72:75], v[212:215], v[240:243], v[28:31]
	v_mfma_f32_16x16x32_bf16 v[28:31], v[216:219], v[236:239], v[58:61]
	v_mfma_f32_16x16x32_bf16 v[136:139], v[212:215], v[62:65], v[66:69]
	v_mfma_f32_16x16x32_bf16 v[68:71], v[188:191], v[240:243], v[28:31]
	s_setprio 0
	s_barrier
	ds_read_b128 v[36:39], v187 offset:49152
	ds_read_b128 v[40:43], v187 offset:50176
	ds_read_b128 v[112:115], v187 offset:51200
	ds_read_b128 v[220:223], v187 offset:52224
	ds_read_b128 v[224:227], v187 offset:53248
	ds_read_b128 v[228:231], v187 offset:54272
	ds_read_b128 v[232:235], v187 offset:55296
	ds_read_b128 v[236:239], v187 offset:56320
	s_add_u32 s12, s6, 0x180
	s_addc_u32 s13, s7, 0
	s_mov_b32 m0, s34
	s_nop 0
	global_load_lds_dwordx4 v175, s[12:13]
	s_nop 0
	s_mov_b32 m0, s35
	s_nop 0
	global_load_lds_dwordx4 v177, s[12:13]
	s_add_u32 s12, s6, 0x160180
	s_addc_u32 s13, s7, 0
	s_mov_b32 m0, s40
	s_nop 0
	global_load_lds_dwordx4 v175, s[12:13]
	s_nop 0
	s_mov_b32 m0, s41
	s_nop 0
	global_load_lds_dwordx4 v177, s[12:13]
	s_nop 0
	s_mov_b32 m0, s36
	s_nop 0
	global_load_lds_dwordx4 v174, s[10:11]
	s_nop 0
	s_mov_b32 m0, s37
	s_nop 0
	global_load_lds_dwordx4 v176, s[10:11]
	s_waitcnt vmcnt(8)
	s_waitcnt lgkmcnt(0)
	s_barrier
	s_setprio 1
	s_waitcnt lgkmcnt(0)
	v_mfma_f32_16x16x32_bf16 v[28:31], v[10:13], v[36:39], v[132:135]
	v_mfma_f32_16x16x32_bf16 v[64:67], v[14:17], v[40:43], v[28:31]
	v_mfma_f32_16x16x32_bf16 v[28:31], v[20:23], v[36:39], v[148:151]
	v_mfma_f32_16x16x32_bf16 v[60:63], v[24:27], v[40:43], v[28:31]
	v_mfma_f32_16x16x32_bf16 v[28:31], v[10:13], v[112:115], v[152:155]
	v_mfma_f32_16x16x32_bf16 v[48:51], v[14:17], v[220:223], v[28:31]
	v_mfma_f32_16x16x32_bf16 v[28:31], v[20:23], v[112:115], v[156:159]
	v_mfma_f32_16x16x32_bf16 v[44:47], v[24:27], v[220:223], v[28:31]
	v_mfma_f32_16x16x32_bf16 v[28:31], v[10:13], v[224:227], v[160:163]
	v_mfma_f32_16x16x32_bf16 v[2:5], v[10:13], v[232:235], v[2:5]
	v_mfma_f32_16x16x32_bf16 v[32:35], v[14:17], v[228:231], v[28:31]
	v_mfma_f32_16x16x32_bf16 v[28:31], v[20:23], v[224:227], v[164:167]
	v_mfma_f32_16x16x32_bf16 v[16:19], v[14:17], v[236:239], v[2:5]
	v_mfma_f32_16x16x32_bf16 v[2:5], v[20:23], v[232:235], v[6:9]
	v_mfma_f32_16x16x32_bf16 v[28:31], v[24:27], v[228:231], v[28:31]
	v_mfma_f32_16x16x32_bf16 v[12:15], v[24:27], v[236:239], v[2:5]
	s_setprio 0
	s_setprio 1
	v_mfma_f32_16x16x32_bf16 v[2:5], v[208:211], v[36:39], v[168:171]
	v_mfma_f32_16x16x32_bf16 v[56:59], v[212:215], v[40:43], v[2:5]
	v_mfma_f32_16x16x32_bf16 v[2:5], v[216:219], v[36:39], v[178:181]
	v_mfma_f32_16x16x32_bf16 v[52:55], v[188:191], v[40:43], v[2:5]
	v_mfma_f32_16x16x32_bf16 v[2:5], v[208:211], v[112:115], v[192:195]
	v_mfma_f32_16x16x32_bf16 v[40:43], v[212:215], v[220:223], v[2:5]
	v_mfma_f32_16x16x32_bf16 v[2:5], v[216:219], v[112:115], v[196:199]
	v_mfma_f32_16x16x32_bf16 v[36:39], v[188:191], v[220:223], v[2:5]
	v_mfma_f32_16x16x32_bf16 v[2:5], v[208:211], v[224:227], v[200:203]
	v_mfma_f32_16x16x32_bf16 v[24:27], v[212:215], v[228:231], v[2:5]
	v_mfma_f32_16x16x32_bf16 v[2:5], v[216:219], v[224:227], v[120:123]
	v_mfma_f32_16x16x32_bf16 v[20:23], v[188:191], v[228:231], v[2:5]
	v_mfma_f32_16x16x32_bf16 v[2:5], v[208:211], v[232:235], v[204:207]
	v_mfma_f32_16x16x32_bf16 v[8:11], v[212:215], v[236:239], v[2:5]
	v_mfma_f32_16x16x32_bf16 v[2:5], v[216:219], v[232:235], v[124:127]
	v_mfma_f32_16x16x32_bf16 v[4:7], v[188:191], v[236:239], v[2:5]
	s_setprio 0
	s_barrier
	s_mov_b64 s[12:13], 0
	s_branch .LBB0_1209

; #define GAS __attribute__((address_space(1)))
; __device__ __forceinline__ float xlo(unsigned w) { if (XRES_F16) { const f16x2_t h = __builtin_bit_cast(f16x2_t, w); return (float)h[0]; } return __builtin_bit_cast(float, w << 16); }
; __device__ __forceinline__ float xhi(unsigned w) { if (XRES_F16) { const f16x2_t h = __builtin_bit_cast(f16x2_t, w); return (float)h[1]; } return __builtin_bit_cast(float, w & 0xffff0000u); }
; template <int CTRL> __device__ __forceinline__ float dpp_mov(float v) { return __builtin_bit_cast(float, __builtin_amdgcn_update_dpp(0, __builtin_bit_cast(int, v), CTRL, 0xF, 0xF, true)); }
; __device__ __forceinline__ float wave_sum(float v) {
;     v += dpp_mov<0xB1>(v);
;     v += dpp_mov<0x4E>(v);
;     v += dpp_mov<0x141>(v);
;     v += dpp_mov<0x140>(v);
;     const int iv = __builtin_bit_cast(int, v);
;     const float a = __builtin_bit_cast(float, __builtin_amdgcn_readlane(iv, 0)), b = __builtin_bit_cast(float, __builtin_amdgcn_readlane(iv, 16));
;     const float c = __builtin_bit_cast(float, __builtin_amdgcn_readlane(iv, 32)), d = __builtin_bit_cast(float, __builtin_amdgcn_readlane(iv, 48));
;     return (a + b) + (c + d);
; }
; __device__ __forceinline__ void final_norm_phase(const Args& a, Frame& F) {
;     ...
;     for (int r = gw; r < ML; r += NGW) {
;         const GAS v2u* xr = (const GAS v2u*)(X + (size_t)r * D) + F.lane;
;         f32x4 v[8]; float ss = 0.f;
; #pragma unroll
;         for (int j = 0; j < 8; ++j) { const v2u w = xr[64 * j]; v[j] = (f32x4){xlo(w.x), xhi(w.x), xlo(w.y), xhi(w.y)}; ss += (v[j][0] * v[j][0] + v[j][1] * v[j][1]) + (v[j][2] * v[j][2] + v[j][3] * v[j][3]); }
;         const float rstd = 1.0f / sqrtf(wave_sum(ss) * (1.0f / D) + EPS);
;         GAS f32x4* o = (GAS f32x4*)(a.out + (size_t)r * D) + F.lane;
; #pragma unroll
;         for (int j = 0; j < 8; ++j) o[64 * j] = (v[j] * rstd) * *(const GAS f32x4*)(gain + 256 * j + 4 * F.lane);
.LBB0_1333:
	global_load_dwordx2 v[20:21], v[12:13], off offset:-2048
	global_load_dwordx2 v[22:23], v[12:13], off offset:-1536
	global_load_dwordx2 v[24:25], v[12:13], off offset:-1024
	global_load_dwordx2 v[26:27], v[12:13], off offset:-512
	global_load_dwordx2 v[28:29], v[12:13], off
	global_load_dwordx2 v[30:31], v[12:13], off offset:512
	global_load_dwordx2 v[32:33], v[12:13], off offset:1024
	global_load_dwordx2 v[34:35], v[12:13], off offset:1536
	global_load_dwordx4 v[16:19], v[0:1], off
	s_add_i32 s4, s4, s42
	v_lshl_add_u64 v[12:13], v[12:13], 0, s[74:75]
	s_cmpk_lt_i32 s4, 0x4000
	s_waitcnt vmcnt(8)
	v_cvt_f32_f16_sdwa v37, v20 dst_sel:DWORD dst_unused:UNUSED_PAD src0_sel:WORD_1
	v_cvt_f32_f16_e32 v36, v20
	v_cvt_f32_f16_sdwa v39, v21 dst_sel:DWORD dst_unused:UNUSED_PAD src0_sel:WORD_1
	v_cvt_f32_f16_e32 v38, v21
	s_waitcnt vmcnt(7)
	v_cvt_f32_f16_e32 v21, v23
	v_cvt_f32_f16_e32 v20, v22
	v_cvt_f32_f16_sdwa v23, v23 dst_sel:DWORD dst_unused:UNUSED_PAD src0_sel:WORD_1
	v_cvt_f32_f16_sdwa v22, v22 dst_sel:DWORD dst_unused:UNUSED_PAD src0_sel:WORD_1
	s_waitcnt vmcnt(6)
	v_cvt_f32_f16_sdwa v41, v24 dst_sel:DWORD dst_unused:UNUSED_PAD src0_sel:WORD_1
	v_cvt_f32_f16_sdwa v43, v25 dst_sel:DWORD dst_unused:UNUSED_PAD src0_sel:WORD_1
	v_cvt_f32_f16_e32 v40, v24
	v_cvt_f32_f16_e32 v42, v25
	s_waitcnt vmcnt(5)
	v_cvt_f32_f16_sdwa v25, v26 dst_sel:DWORD dst_unused:UNUSED_PAD src0_sel:WORD_1
	v_cvt_f32_f16_e32 v24, v26
	v_cvt_f32_f16_sdwa v45, v27 dst_sel:DWORD dst_unused:UNUSED_PAD src0_sel:WORD_1
	v_cvt_f32_f16_e32 v44, v27
	s_waitcnt vmcnt(4)
	v_cvt_f32_f16_e32 v27, v29
	v_cvt_f32_f16_e32 v26, v28
	v_cvt_f32_f16_sdwa v29, v29 dst_sel:DWORD dst_unused:UNUSED_PAD src0_sel:WORD_1
	v_cvt_f32_f16_sdwa v28, v28 dst_sel:DWORD dst_unused:UNUSED_PAD src0_sel:WORD_1
	s_waitcnt vmcnt(2)
	v_cvt_f32_f16_sdwa v49, v32 dst_sel:DWORD dst_unused:UNUSED_PAD src0_sel:WORD_1
	v_cvt_f32_f16_e32 v48, v32
	v_cvt_f32_f16_sdwa v51, v33 dst_sel:DWORD dst_unused:UNUSED_PAD src0_sel:WORD_1
	v_cvt_f32_f16_e32 v50, v33
	s_waitcnt vmcnt(1)
	v_cvt_f32_f16_sdwa v33, v34 dst_sel:DWORD dst_unused:UNUSED_PAD src0_sel:WORD_1
	v_cvt_f32_f16_e32 v32, v34
	v_mul_f32_e32 v34, v37, v37
	v_mul_f32_e32 v54, v39, v39
	v_mul_f32_e32 v56, v22, v22
	v_mul_f32_e32 v57, v23, v23
	v_cvt_f32_f16_e32 v47, v31
	v_cvt_f32_f16_e32 v46, v30
	v_cvt_f32_f16_sdwa v31, v31 dst_sel:DWORD dst_unused:UNUSED_PAD src0_sel:WORD_1
	v_cvt_f32_f16_sdwa v30, v30 dst_sel:DWORD dst_unused:UNUSED_PAD src0_sel:WORD_1
	v_cvt_f32_f16_sdwa v53, v35 dst_sel:DWORD dst_unused:UNUSED_PAD src0_sel:WORD_1
	v_cvt_f32_f16_e32 v52, v35
	v_mul_f32_e32 v58, v41, v41
	v_mul_f32_e32 v60, v43, v43
	v_fma_f32 v35, v37, v37, v34
	v_fma_f32 v34, v36, v36, v34
	v_fma_f32 v55, v39, v39, v54
	v_fma_f32 v54, v38, v38, v54
	v_fma_f32 v56, v20, v20, v56
	v_fma_f32 v57, v21, v21, v57
	v_mul_f32_e32 v62, v24, v24
	v_mul_f32_e32 v63, v25, v25
	v_mul_f32_e32 v64, v44, v44
	v_mul_f32_e32 v65, v45, v45
	v_fma_f32 v59, v41, v41, v58
	v_fma_f32 v58, v40, v40, v58
	v_fma_f32 v61, v43, v43, v60
	v_fma_f32 v60, v42, v42, v60
	v_pk_add_f32 v[56:57], v[56:57], v[56:57] op_sel:[0,1] op_sel_hi:[1,0]
	v_add_f32_e32 v34, v34, v54
	v_add_f32_e32 v35, v35, v55
	v_mov_b32_e32 v59, v64
	v_mov_b32_e32 v61, v65
	v_mov_b32_e32 v35, v62
	v_mov_b32_e32 v57, v63
	v_mul_f32_e32 v66, v28, v28
	v_mul_f32_e32 v67, v29, v29
	v_add_f32_e32 v58, v58, v60
	v_add_f32_e32 v59, v59, v61
	v_add_f32_e32 v34, v34, v56
	v_add_f32_e32 v35, v35, v57
	v_mul_f32_e32 v68, v30, v30
	v_mul_f32_e32 v69, v31, v31
	v_fma_f32 v66, v26, v26, v66
	v_fma_f32 v67, v27, v27, v67
	v_add_f32_e32 v34, v34, v58
	v_add_f32_e32 v35, v35, v59
	v_mul_f32_e32 v70, v49, v49
	v_mul_f32_e32 v72, v51, v51
	v_fma_f32 v68, v46, v46, v68
	v_fma_f32 v69, v47, v47, v69
	v_add_f32_e32 v54, v66, v67
	v_add_f32_e32 v55, v67, v66
	v_pk_add_f32 v[34:35], v[34:35], v[34:35] op_sel:[0,1] op_sel_hi:[1,0]
	v_mul_f32_e32 v74, v32, v32
	v_mul_f32_e32 v75, v33, v33
	v_mul_f32_e32 v76, v52, v52
	v_mul_f32_e32 v77, v53, v53
	v_fma_f32 v71, v49, v49, v70
	v_fma_f32 v70, v48, v48, v70
	v_fma_f32 v73, v51, v51, v72
	v_fma_f32 v72, v50, v50, v72
	v_add_f32_e32 v64, v68, v69
	v_add_f32_e32 v65, v69, v68
	v_add_f32_e32 v34, v34, v54
	v_add_f32_e32 v35, v35, v55
	v_mov_b32_e32 v71, v76
	v_mov_b32_e32 v73, v77
	v_mov_b32_e32 v65, v75
	v_mov_b32_e32 v35, v74
	v_add_f32_e32 v60, v70, v72
	v_add_f32_e32 v61, v71, v73
	v_add_f32_e32 v34, v34, v64
	v_add_f32_e32 v35, v35, v65
	s_nop 0
	v_add_f32_e32 v34, v34, v60
	v_add_f32_e32 v35, v35, v61
	s_nop 0
	v_add_f32_e32 v34, v34, v35
	s_nop 1
	v_add_f32_dpp v34, v34, v34 quad_perm:[1,0,3,2] row_mask:0xf bank_mask:0xf bound_ctrl:1
	s_nop 1
	v_add_f32_dpp v34, v34, v34 quad_perm:[2,3,0,1] row_mask:0xf bank_mask:0xf bound_ctrl:1
	s_nop 1
	v_add_f32_dpp v34, v34, v34 row_half_mirror row_mask:0xf bank_mask:0xf bound_ctrl:1
	s_nop 1
	v_add_f32_dpp v34, v34, v34 row_mirror row_mask:0xf bank_mask:0xf bound_ctrl:1
	s_nop 0
	v_readlane_b32 s6, v34, 16
	v_readlane_b32 s7, v34, 48
	v_readlane_b32 s0, v34, 0
	v_readlane_b32 s1, v34, 32
	v_mov_b32_e32 v34, s6
	v_mov_b32_e32 v35, s7
	v_add_f32_e32 v34, s0, v34
	v_add_f32_e32 v35, s1, v35
	s_nop 0
	v_add_f32_e32 v34, v34, v35
	v_fmamk_f32 v34, v34, 0x3a000000, v14
	v_mul_f32_e32 v35, 0x4f800000, v34
	v_cmp_gt_f32_e32 vcc, s5, v34
	s_nop 1
	v_cndmask_b32_e32 v34, v34, v35, vcc
	v_sqrt_f32_e32 v35, v34
	s_nop 0
	v_add_u32_e32 v54, -1, v35
	v_add_u32_e32 v55, 1, v35
	v_fma_f32 v56, -v54, v35, v34
	v_fma_f32 v57, -v55, v35, v34
	v_cmp_ge_f32_e64 s[0:1], 0, v56
	s_nop 1
	v_cndmask_b32_e64 v35, v35, v54, s[0:1]
	v_cmp_lt_f32_e64 s[0:1], 0, v57
	s_nop 1
	v_cndmask_b32_e64 v35, v35, v55, s[0:1]
	v_mul_f32_e32 v54, 0x37800000, v35
	v_cndmask_b32_e32 v35, v35, v54, vcc
	v_cmp_class_f32_e32 vcc, v34, v15
	s_nop 1
	v_cndmask_b32_e32 v34, v35, v34, vcc
	v_div_scale_f32 v35, s[0:1], v34, v34, 1.0
	v_rcp_f32_e32 v55, v35
	v_div_scale_f32 v54, vcc, 1.0, v34, 1.0
	v_fma_f32 v56, -v35, v55, 1.0
	v_fmac_f32_e32 v55, v56, v55
	v_mul_f32_e32 v56, v54, v55
	v_fma_f32 v57, -v35, v56, v54
	v_fmac_f32_e32 v56, v57, v55
	v_fma_f32 v35, -v35, v56, v54
	v_div_fmas_f32 v35, v35, v55, v56
	v_div_fixup_f32 v34, v35, v34, 1.0
	v_mul_f32_e32 v36, v36, v34
	v_mul_f32_e32 v37, v37, v34
	v_mul_f32_e32 v38, v38, v34
	v_mul_f32_e32 v39, v39, v34
	s_waitcnt vmcnt(0)
; #define GAS __attribute__((address_space(1)))
; __device__ __forceinline__ void final_norm_phase(const Args& a, Frame& F) {
;     ...
;         GAS f32x4* o = (GAS f32x4*)(a.out + (size_t)r * D) + F.lane;
; #pragma unroll
;         for (int j = 0; j < 8; ++j) o[64 * j] = (v[j] * rstd) * *(const GAS f32x4*)(gain + 256 * j + 4 * F.lane);
	v_mul_f32_e32 v16, v16, v36
	v_mul_f32_e32 v17, v17, v37
	v_mul_f32_e32 v18, v18, v38
	v_mul_f32_e32 v19, v19, v39
	global_store_dwordx4 v[10:11], v[16:19], off offset:-4096
	global_load_dwordx4 v[16:19], v[0:1], off offset:1024
	v_mov_b32_e32 v36, v21
	v_mov_b32_e32 v37, v23
	v_mov_b32_e32 v21, v22
	v_mul_f32_e32 v22, v36, v34
	v_mul_f32_e32 v23, v37, v34
	v_mul_f32_e32 v20, v20, v34
	v_mul_f32_e32 v21, v21, v34
	s_waitcnt vmcnt(0)
	v_mul_f32_e32 v18, v18, v22
	v_mul_f32_e32 v19, v19, v23
	v_mul_f32_e32 v16, v16, v20
	v_mul_f32_e32 v17, v17, v21
	global_store_dwordx4 v[10:11], v[16:19], off offset:-3072
	global_load_dwordx4 v[16:19], v[0:1], off offset:2048
	v_mul_f32_e32 v20, v42, v34
	v_mul_f32_e32 v21, v43, v34
	v_mul_f32_e32 v22, v40, v34
	v_mul_f32_e32 v23, v41, v34
	s_waitcnt vmcnt(0)
	v_mul_f32_e32 v18, v18, v20
	v_mul_f32_e32 v19, v19, v21
	v_mul_f32_e32 v16, v16, v22
	v_mul_f32_e32 v17, v17, v23
	global_store_dwordx4 v[10:11], v[16:19], off offset:-2048
	global_load_dwordx4 v[16:19], v[0:1], off offset:3072
	v_mul_f32_e32 v20, v44, v34
	v_mul_f32_e32 v21, v45, v34
	v_mul_f32_e32 v22, v24, v34
	v_mul_f32_e32 v23, v25, v34
	s_waitcnt vmcnt(0)
	v_mul_f32_e32 v18, v18, v20
	v_mul_f32_e32 v19, v19, v21
	v_mul_f32_e32 v16, v16, v22
	v_mul_f32_e32 v17, v17, v23
	global_store_dwordx4 v[10:11], v[16:19], off offset:-1024
	global_load_dwordx4 v[16:19], v[2:3], off
	v_mov_b32_e32 v20, v27
	v_mov_b32_e32 v21, v29
	v_mov_b32_e32 v27, v28
	v_mul_f32_e32 v20, v20, v34
	v_mul_f32_e32 v21, v21, v34
	v_mul_f32_e32 v22, v26, v34
	v_mul_f32_e32 v23, v27, v34
	s_waitcnt vmcnt(0)
	v_mul_f32_e32 v18, v18, v20
	v_mul_f32_e32 v19, v19, v21
	v_mul_f32_e32 v16, v16, v22
	v_mul_f32_e32 v17, v17, v23
	global_store_dwordx4 v[10:11], v[16:19], off
	global_load_dwordx4 v[16:19], v[4:5], off
	v_mov_b32_e32 v20, v47
	v_mov_b32_e32 v21, v31
	v_mov_b32_e32 v47, v30
	v_mul_f32_e32 v20, v20, v34
	v_mul_f32_e32 v21, v21, v34
	v_mul_f32_e32 v22, v46, v34
	v_mul_f32_e32 v23, v47, v34
	s_waitcnt vmcnt(0)
	v_mul_f32_e32 v18, v20, v18
	v_mul_f32_e32 v19, v21, v19
	v_mul_f32_e32 v16, v22, v16
	v_mul_f32_e32 v17, v23, v17
	global_store_dwordx4 v[10:11], v[16:19], off offset:1024
	global_load_dwordx4 v[16:19], v[6:7], off
	v_mul_f32_e32 v20, v50, v34
	v_mul_f32_e32 v21, v51, v34
	v_mul_f32_e32 v22, v48, v34
	v_mul_f32_e32 v23, v49, v34
	s_waitcnt vmcnt(0)
	v_mul_f32_e32 v18, v20, v18
	v_mul_f32_e32 v19, v21, v19
	v_mul_f32_e32 v16, v22, v16
	v_mul_f32_e32 v17, v23, v17
	global_store_dwordx4 v[10:11], v[16:19], off offset:2048
	global_load_dwordx4 v[16:19], v[8:9], off
	v_mul_f32_e32 v20, v52, v34
	v_mul_f32_e32 v21, v53, v34
	v_mul_f32_e32 v22, v32, v34
	v_mul_f32_e32 v23, v33, v34
	s_waitcnt vmcnt(0)
	v_mul_f32_e32 v18, v20, v18
	v_mul_f32_e32 v19, v21, v19
	v_mul_f32_e32 v16, v22, v16
	v_mul_f32_e32 v17, v23, v17
	global_store_dwordx4 v[10:11], v[16:19], off offset:3072
	v_lshl_add_u64 v[10:11], v[10:11], 0, s[2:3]
	s_cbranch_scc1 .LBB0_1333

; #define GAS __attribute__((address_space(1)))
; #define LAS __attribute__((address_space(3)))
; #define FN_LOAD(dst, k_) do { const GAS v2u* xr_ = (const GAS v2u*)(X + (size_t)(nw + 2048 * (k_)) * D) + F.lane; \
;         _Pragma("unroll") for (int j = 0; j < 8; ++j) dst[j] = __builtin_nontemporal_load(xr_ + 64 * j); } while (0)
; __device__ __forceinline__ void final_norm_phase2(const Args& a, Frame& F) {
;     ...
;     FN_LOAD(r0, 0); FN_LOAD(r1, 1); FN_LOAD(r2, 2); FN_LOAD(r3, 3); FN_LOAD(r4, 4); FN_LOAD(r5, 5); FN_LOAD(r6, 6); FN_LOAD(r7, 7);
;     for (int q = F.tid; q < D / 4; q += NWAVES * 64) ((LAS f32x4*)GL)[q] = ((const GAS f32x4*)gain)[q];
;     asm volatile("s_waitcnt lgkmcnt(0)" ::: "memory"); __builtin_amdgcn_s_barrier(); asm volatile("" ::: "memory");
;     FN_FINISH(r0, 0); FN_FINISH(r1, 1); FN_FINISH(r2, 2); FN_FINISH(r3, 3); FN_FINISH(r4, 4); FN_FINISH(r5, 5); FN_FINISH(r6, 6); FN_FINISH(r7, 7);
.LBB0_1339:
	s_or_b64 exec, exec, s[10:11]
	s_waitcnt vmcnt(0)
	v_cvt_f32_f16_sdwa v17, v14 dst_sel:DWORD dst_unused:UNUSED_PAD src0_sel:WORD_1
	v_cvt_f32_f16_sdwa v21, v15 dst_sel:DWORD dst_unused:UNUSED_PAD src0_sel:WORD_1
	v_cvt_f32_f16_e32 v20, v15
	v_cvt_f32_f16_sdwa v15, v12 dst_sel:DWORD dst_unused:UNUSED_PAD src0_sel:WORD_1
	v_cvt_f32_f16_e32 v16, v14
	v_cvt_f32_f16_e32 v14, v12
	v_cvt_f32_f16_sdwa v23, v13 dst_sel:DWORD dst_unused:UNUSED_PAD src0_sel:WORD_1
	v_cvt_f32_f16_e32 v22, v13
	v_mov_b32_e32 v24, v17
	v_mov_b32_e32 v25, v15
	v_mov_b32_e32 v12, v16
	v_mov_b32_e32 v13, v14
	v_mul_f32_e32 v24, v24, v24
	v_mul_f32_e32 v25, v25, v25
	v_mov_b32_e32 v26, v21
	v_mov_b32_e32 v27, v23
	v_fma_f32 v12, v12, v12, v24
	v_fma_f32 v13, v13, v13, v25
	v_mov_b32_e32 v24, v20
	v_mov_b32_e32 v25, v22
	v_mul_f32_e32 v26, v26, v26
	v_mul_f32_e32 v27, v27, v27
	v_cvt_f32_f16_sdwa v31, v9 dst_sel:DWORD dst_unused:UNUSED_PAD src0_sel:WORD_1
	v_fma_f32 v24, v24, v24, v26
	v_fma_f32 v25, v25, v25, v27
	v_cvt_f32_f16_sdwa v27, v11 dst_sel:DWORD dst_unused:UNUSED_PAD src0_sel:WORD_1
	v_add_f32_e32 v12, v12, v24
	v_add_f32_e32 v13, v13, v25
	v_cvt_f32_f16_sdwa v25, v10 dst_sel:DWORD dst_unused:UNUSED_PAD src0_sel:WORD_1
	v_cvt_f32_f16_e32 v24, v10
	v_cvt_f32_f16_e32 v26, v11
	v_mov_b32_e32 v29, v27
	v_mov_b32_e32 v28, v25
	v_mov_b32_e32 v10, v24
	v_mov_b32_e32 v11, v26
	v_mul_f32_e32 v28, v28, v28
	v_mul_f32_e32 v29, v29, v29
	v_cvt_f32_f16_e32 v30, v9
	v_fma_f32 v10, v10, v10, v28
	v_fma_f32 v11, v11, v11, v29
	v_cvt_f32_f16_sdwa v29, v8 dst_sel:DWORD dst_unused:UNUSED_PAD src0_sel:WORD_1
	v_cvt_f32_f16_e32 v28, v8
	v_cvt_f32_f16_sdwa v157, v7 dst_sel:DWORD dst_unused:UNUSED_PAD src0_sel:WORD_1
	v_cvt_f32_f16_e32 v156, v7
	v_cvt_f32_f16_sdwa v155, v6 dst_sel:DWORD dst_unused:UNUSED_PAD src0_sel:WORD_1
	v_cvt_f32_f16_e32 v154, v6
	v_cvt_f32_f16_sdwa v159, v4 dst_sel:DWORD dst_unused:UNUSED_PAD src0_sel:WORD_1
	v_cvt_f32_f16_sdwa v161, v5 dst_sel:DWORD dst_unused:UNUSED_PAD src0_sel:WORD_1
	v_mul_f32_e32 v8, v29, v29
	v_mul_f32_e32 v6, v31, v31
	v_cvt_f32_f16_e32 v158, v4
	v_cvt_f32_f16_e32 v160, v5
	v_fma_f32 v9, v29, v29, v8
	v_fma_f32 v8, v28, v28, v8
	v_fma_f32 v7, v31, v31, v6
	v_fma_f32 v6, v30, v30, v6
	v_mul_f32_e32 v146, v156, v156
	v_mul_f32_e32 v147, v157, v157
	v_cvt_f32_f16_sdwa v163, v2 dst_sel:DWORD dst_unused:UNUSED_PAD src0_sel:WORD_1
	v_cvt_f32_f16_sdwa v165, v3 dst_sel:DWORD dst_unused:UNUSED_PAD src0_sel:WORD_1
	v_pk_add_f32 v[12:13], v[12:13], v[12:13] op_sel:[0,1] op_sel_hi:[1,0]
	v_pk_add_f32 v[10:11], v[10:11], v[10:11] op_sel:[0,1] op_sel_hi:[1,0]
	v_mul_f32_e32 v48, v154, v154
	v_mul_f32_e32 v49, v155, v155
	v_mov_b32_e32 v9, v146
	v_mov_b32_e32 v7, v147
	v_cvt_f32_f16_e32 v162, v2
	v_cvt_f32_f16_e32 v164, v3
	v_cvt_f32_f16_sdwa v147, v0 dst_sel:DWORD dst_unused:UNUSED_PAD src0_sel:WORD_1
	v_cvt_f32_f16_e32 v146, v0
	v_cvt_f32_f16_sdwa v149, v1 dst_sel:DWORD dst_unused:UNUSED_PAD src0_sel:WORD_1
	v_cvt_f32_f16_e32 v148, v1
	v_mov_b32_e32 v13, v48
	v_mov_b32_e32 v11, v49
	v_add_f32_e32 v6, v8, v6
	v_add_f32_e32 v7, v9, v7
	v_mov_b32_e32 v8, v159
	v_mov_b32_e32 v9, v161
	v_add_f32_e32 v10, v12, v10
	v_add_f32_e32 v11, v13, v11
	v_mov_b32_e32 v4, v158
	v_mov_b32_e32 v5, v160
	v_mul_f32_e32 v8, v8, v8
	v_mul_f32_e32 v9, v9, v9
	v_add_f32_e32 v6, v10, v6
	v_add_f32_e32 v7, v11, v7
	v_fma_f32 v4, v4, v4, v8
	v_fma_f32 v5, v5, v5, v9
	v_mul_f32_e32 v2, v163, v163
	v_mul_f32_e32 v0, v165, v165
	v_pk_add_f32 v[6:7], v[6:7], v[6:7] op_sel:[0,1] op_sel_hi:[1,0]
	v_pk_add_f32 v[4:5], v[4:5], v[4:5] op_sel:[0,1] op_sel_hi:[1,0]
	v_fma_f32 v3, v163, v163, v2
	v_fma_f32 v2, v162, v162, v2
	v_fma_f32 v1, v165, v165, v0
	v_fma_f32 v0, v164, v164, v0
	v_mul_f32_e32 v8, v146, v146
	v_mul_f32_e32 v9, v147, v147
	v_mul_f32_e32 v10, v148, v148
	v_mul_f32_e32 v11, v149, v149
	v_mov_b32_e32 v7, v8
	v_mov_b32_e32 v5, v9
	v_mov_b32_e32 v3, v10
	v_mov_b32_e32 v1, v11
	v_add_f32_e32 v4, v6, v4
	v_add_f32_e32 v5, v7, v5
	v_add_f32_e32 v0, v2, v0
	v_add_f32_e32 v1, v3, v1
	s_lshl_b64 s[10:11], s[6:7], 11
	v_add_f32_e32 v0, v4, v0
	v_add_f32_e32 v1, v5, v1
	s_lshl_b64 s[6:7], s[18:19], 11
	v_add_f32_e32 v0, v0, v1
	s_lshl_b64 s[16:17], s[0:1], 11
	v_mov_b32_e32 v151, 0x358637bd
	v_add_f32_dpp v0, v0, v0 quad_perm:[1,0,3,2] row_mask:0xf bank_mask:0xf bound_ctrl:1
	v_mov_b32_e32 v152, 0x260
	v_lshlrev_b32_e32 v48, 4, v18
	v_add_f32_dpp v0, v0, v0 quad_perm:[2,3,0,1] row_mask:0xf bank_mask:0xf bound_ctrl:1
	s_waitcnt lgkmcnt(0)
	s_barrier
; template <int CTRL> __device__ __forceinline__ float dpp_mov(float v) { return __builtin_bit_cast(float, __builtin_amdgcn_update_dpp(0, __builtin_bit_cast(int, v), CTRL, 0xF, 0xF, true)); }
; __device__ __forceinline__ float wave_sum(float v) {
;     v += dpp_mov<0xB1>(v);
;     v += dpp_mov<0x4E>(v);
;     v += dpp_mov<0x141>(v);
;     v += dpp_mov<0x140>(v);
;     const int iv = __builtin_bit_cast(int, v);
;     const float a = __builtin_bit_cast(float, __builtin_amdgcn_readlane(iv, 0)), b = __builtin_bit_cast(float, __builtin_amdgcn_readlane(iv, 16));
;     const float c = __builtin_bit_cast(float, __builtin_amdgcn_readlane(iv, 32)), d = __builtin_bit_cast(float, __builtin_amdgcn_readlane(iv, 48));
;     return (a + b) + (c + d);
; }
	v_add_u32_e32 v153, 0, v48
	v_add_f32_dpp v0, v0, v0 row_half_mirror row_mask:0xf bank_mask:0xf bound_ctrl:1
	s_lshl_b64 s[14:15], s[2:3], 11
	s_lshl_b64 s[12:13], s[4:5], 11
	v_add_f32_dpp v0, v0, v0 row_mirror row_mask:0xf bank_mask:0xf bound_ctrl:1
	s_lshl_b64 s[8:9], s[8:9], 11
	v_readlane_b32 s18, v0, 16
	v_readlane_b32 s19, v0, 48
	v_readlane_b32 s0, v0, 0
	v_readlane_b32 s1, v0, 32
	v_mov_b32_e32 v0, s18
	v_mov_b32_e32 v1, s19
	v_add_f32_e32 v0, s0, v0
	v_add_f32_e32 v1, s1, v1
	s_mov_b32 s18, 0xf800000
	v_add_f32_e32 v0, v0, v1
	v_fmamk_f32 v0, v0, 0x3a000000, v151
	v_mul_f32_e32 v1, 0x4f800000, v0
	v_cmp_gt_f32_e32 vcc, s18, v0
	s_lshl_b64 s[4:5], s[20:21], 11
	s_lshl_b64 s[2:3], s[22:23], 11
	v_cndmask_b32_e32 v0, v0, v1, vcc
	v_sqrt_f32_e32 v1, v0
	v_mov_b32_e32 v49, 0
	v_cvt_f32_f16_sdwa v173, v139 dst_sel:DWORD dst_unused:UNUSED_PAD src0_sel:WORD_1
	v_cvt_f32_f16_e32 v172, v139
	v_add_u32_e32 v2, -1, v1
	v_fma_f32 v3, -v2, v1, v0
	v_cmp_ge_f32_e64 s[0:1], 0, v3
	v_add_u32_e32 v3, 1, v1
	v_cvt_f32_f16_sdwa v175, v136 dst_sel:DWORD dst_unused:UNUSED_PAD src0_sel:WORD_1
	v_cndmask_b32_e64 v2, v1, v2, s[0:1]
	v_fma_f32 v1, -v3, v1, v0
	v_cmp_lt_f32_e64 s[0:1], 0, v1
	v_cvt_f32_f16_e32 v174, v136
	v_cvt_f32_f16_sdwa v177, v137 dst_sel:DWORD dst_unused:UNUSED_PAD src0_sel:WORD_1
	v_cndmask_b32_e64 v1, v2, v3, s[0:1]
	v_mul_f32_e32 v2, 0x37800000, v1
	v_cndmask_b32_e32 v1, v1, v2, vcc
	v_cmp_class_f32_e32 vcc, v0, v152
	v_cvt_f32_f16_e32 v176, v137
	v_mul_f32_e32 v136, v173, v173
	v_cndmask_b32_e32 v0, v1, v0, vcc
	v_div_scale_f32 v1, s[0:1], v0, v0, 1.0
	v_rcp_f32_e32 v2, v1
	s_lshl_b64 s[0:1], s[16:17], 2
	s_add_u32 s0, s24, s0
	s_addc_u32 s1, s25, s1
	v_fma_f32 v3, -v1, v2, 1.0
	v_fmac_f32_e32 v2, v3, v2
	v_div_scale_f32 v3, vcc, 1.0, v0, 1.0
	v_mul_f32_e32 v4, v3, v2
	v_fma_f32 v5, -v1, v4, v3
	v_fmac_f32_e32 v4, v5, v2
	v_fma_f32 v1, -v1, v4, v3
	v_div_fmas_f32 v1, v1, v2, v4
	v_div_fixup_f32 v150, v1, v0, 1.0
	ds_read_b128 v[0:3], v153
	ds_read_b128 v[4:7], v153 offset:1024
	v_mul_f32_e32 v8, v16, v150
	v_mul_f32_e32 v9, v17, v150
	v_mul_f32_e32 v10, v20, v150
	v_mul_f32_e32 v11, v21, v150
	v_mul_f32_e32 v16, v24, v150
	v_mul_f32_e32 v17, v25, v150
	s_waitcnt lgkmcnt(1)
	v_mul_f32_e32 v10, v2, v10
	v_mul_f32_e32 v11, v3, v11
	v_mul_f32_e32 v8, v0, v8
	v_mul_f32_e32 v9, v1, v9
	global_store_dwordx4 v48, v[8:11], s[0:1]
	v_mul_f32_e32 v18, v26, v150
	v_mul_f32_e32 v19, v27, v150
	v_lshl_add_u64 v[166:167], s[0:1], 0, v[48:49]
	v_mul_f32_e32 v8, v14, v150
	v_mul_f32_e32 v9, v15, v150
	v_mul_f32_e32 v10, v22, v150
	v_mul_f32_e32 v11, v23, v150
	s_waitcnt lgkmcnt(0)
	v_mul_f32_e32 v12, v4, v8
	v_mul_f32_e32 v13, v5, v9
	v_mul_f32_e32 v14, v6, v10
	v_mul_f32_e32 v15, v7, v11
	ds_read_b128 v[8:11], v153 offset:2048
	global_store_dwordx4 v48, v[12:15], s[0:1] offset:1024
	ds_read_b128 v[12:15], v153 offset:3072
	s_movk_i32 s16, 0x1000
	v_mul_f32_e32 v24, v154, v150
	v_mul_f32_e32 v25, v155, v150
	s_waitcnt lgkmcnt(1)
	v_mul_f32_e32 v18, v10, v18
	v_mul_f32_e32 v19, v11, v19
	v_mul_f32_e32 v16, v8, v16
	v_mul_f32_e32 v17, v9, v17
	global_store_dwordx4 v48, v[16:19], s[0:1] offset:2048
	v_mul_f32_e32 v26, v156, v150
	v_mul_f32_e32 v27, v157, v150
	v_add_co_u32_e32 v166, vcc, s16, v166
	v_mul_f32_e32 v16, v28, v150
	v_mul_f32_e32 v17, v29, v150
	v_mul_f32_e32 v18, v30, v150
	v_mul_f32_e32 v19, v31, v150
	s_waitcnt lgkmcnt(0)
	v_mul_f32_e32 v20, v12, v16
	v_mul_f32_e32 v21, v13, v17
	v_mul_f32_e32 v22, v14, v18
	v_mul_f32_e32 v23, v15, v19
	ds_read_b128 v[16:19], v153 offset:4096
	global_store_dwordx4 v48, v[20:23], s[0:1] offset:3072
	ds_read_b128 v[20:23], v153 offset:5120
	v_addc_co_u32_e32 v167, vcc, 0, v167, vcc
	s_waitcnt lgkmcnt(1)
	v_mul_f32_e32 v26, v18, v26
	v_mul_f32_e32 v27, v19, v27
	v_mul_f32_e32 v24, v16, v24
	v_mul_f32_e32 v25, v17, v25
	global_store_dwordx4 v[166:167], v[24:27], off
	v_mul_f32_e32 v154, v162, v150
	v_mul_f32_e32 v155, v163, v150
	v_cvt_f32_f16_sdwa v163, v143 dst_sel:DWORD dst_unused:UNUSED_PAD src0_sel:WORD_1
	v_mul_f32_e32 v24, v158, v150
	v_mul_f32_e32 v25, v159, v150
	v_mul_f32_e32 v26, v160, v150
	v_mul_f32_e32 v27, v161, v150
	v_cvt_f32_f16_sdwa v159, v144 dst_sel:DWORD dst_unused:UNUSED_PAD src0_sel:WORD_1
	v_cvt_f32_f16_sdwa v161, v145 dst_sel:DWORD dst_unused:UNUSED_PAD src0_sel:WORD_1
	v_cvt_f32_f16_e32 v160, v145
	v_cvt_f32_f16_sdwa v145, v142 dst_sel:DWORD dst_unused:UNUSED_PAD src0_sel:WORD_1
	v_cvt_f32_f16_e32 v158, v144
	v_cvt_f32_f16_e32 v144, v142
	v_cvt_f32_f16_e32 v162, v143
	v_mul_f32_e32 v156, v164, v150
	v_mul_f32_e32 v157, v165, v150
	v_mov_b32_e32 v164, v159
	v_mov_b32_e32 v165, v145
	v_mov_b32_e32 v142, v158
	v_mov_b32_e32 v143, v144
	v_mul_f32_e32 v164, v164, v164
	v_mul_f32_e32 v165, v165, v165
	v_mov_b32_e32 v168, v161
	v_mov_b32_e32 v169, v163
	v_fma_f32 v142, v142, v142, v164
	v_fma_f32 v143, v143, v143, v165
	v_mov_b32_e32 v164, v160
	v_mov_b32_e32 v165, v162
	v_mul_f32_e32 v168, v168, v168
	v_mul_f32_e32 v169, v169, v169
	v_fma_f32 v137, v173, v173, v136
	v_fma_f32 v136, v172, v172, v136
	v_fma_f32 v164, v164, v164, v168
	v_fma_f32 v165, v165, v165, v169
	v_cvt_f32_f16_sdwa v169, v141 dst_sel:DWORD dst_unused:UNUSED_PAD src0_sel:WORD_1
	v_add_f32_e32 v142, v142, v164
	v_add_f32_e32 v143, v143, v165
	v_cvt_f32_f16_sdwa v165, v140 dst_sel:DWORD dst_unused:UNUSED_PAD src0_sel:WORD_1
	v_cvt_f32_f16_e32 v164, v140
	v_cvt_f32_f16_e32 v168, v141
	v_mov_b32_e32 v171, v169
	v_mov_b32_e32 v170, v165
	v_mov_b32_e32 v140, v164
	v_mov_b32_e32 v141, v168
	v_mul_f32_e32 v170, v170, v170
	v_mul_f32_e32 v171, v171, v171
	v_pk_add_f32 v[142:143], v[142:143], v[142:143] op_sel:[0,1] op_sel_hi:[1,0]
; #define GAS __attribute__((address_space(1)))
; #define LAS __attribute__((address_space(3)))
; #define FN_LOAD(dst, k_) do { const GAS v2u* xr_ = (const GAS v2u*)(X + (size_t)(nw + 2048 * (k_)) * D) + F.lane; \
;         _Pragma("unroll") for (int j = 0; j < 8; ++j) dst[j] = __builtin_nontemporal_load(xr_ + 64 * j); } while (0)
; __device__ __forceinline__ void final_norm_phase2(const Args& a, Frame& F) {
;     ...
;     FN_LOAD(r0, 0); FN_LOAD(r1, 1); FN_LOAD(r2, 2); FN_LOAD(r3, 3); FN_LOAD(r4, 4); FN_LOAD(r5, 5); FN_LOAD(r6, 6); FN_LOAD(r7, 7);
;     for (int q = F.tid; q < D / 4; q += NWAVES * 64) ((LAS f32x4*)GL)[q] = ((const GAS f32x4*)gain)[q];
;     asm volatile("s_waitcnt lgkmcnt(0)" ::: "memory"); __builtin_amdgcn_s_barrier(); asm volatile("" ::: "memory");
;     FN_FINISH(r0, 0); FN_FINISH(r1, 1); FN_FINISH(r2, 2); FN_FINISH(r3, 3); FN_FINISH(r4, 4); FN_FINISH(r5, 5); FN_FINISH(r6, 6); FN_FINISH(r7, 7);
	v_fma_f32 v140, v140, v140, v170
	v_fma_f32 v141, v141, v141, v171
	v_cvt_f32_f16_sdwa v171, v138 dst_sel:DWORD dst_unused:UNUSED_PAD src0_sel:WORD_1
	v_cvt_f32_f16_e32 v170, v138
	v_pk_add_f32 v[140:141], v[140:141], v[140:141] op_sel:[0,1] op_sel_hi:[1,0]
	v_mul_f32_e32 v178, v174, v174
	v_mul_f32_e32 v179, v175, v175
	v_mul_f32_e32 v138, v171, v171
	v_fma_f32 v139, v171, v171, v138
	v_fma_f32 v138, v170, v170, v138
	v_mul_f32_e32 v180, v176, v176
	v_mul_f32_e32 v181, v177, v177
	v_mov_b32_e32 v143, v178
	v_mov_b32_e32 v141, v179
	v_mov_b32_e32 v139, v180
	v_mov_b32_e32 v137, v181
	v_add_f32_e32 v140, v142, v140
	v_add_f32_e32 v141, v143, v141
	v_add_f32_e32 v136, v138, v136
	v_add_f32_e32 v137, v139, v137
	v_cvt_f32_f16_sdwa v143, v135 dst_sel:DWORD dst_unused:UNUSED_PAD src0_sel:WORD_1
	v_add_f32_e32 v136, v140, v136
	v_add_f32_e32 v137, v141, v137
	v_cvt_f32_f16_sdwa v141, v134 dst_sel:DWORD dst_unused:UNUSED_PAD src0_sel:WORD_1
	v_cvt_f32_f16_e32 v140, v134
	v_cvt_f32_f16_e32 v142, v135
	v_cvt_f32_f16_sdwa v179, v132 dst_sel:DWORD dst_unused:UNUSED_PAD src0_sel:WORD_1
	v_cvt_f32_f16_e32 v178, v132
	v_mov_b32_e32 v138, v141
	v_mov_b32_e32 v139, v143
	v_mov_b32_e32 v134, v140
	v_mov_b32_e32 v135, v142
	v_mul_f32_e32 v138, v138, v138
	v_mul_f32_e32 v139, v139, v139
	v_cvt_f32_f16_sdwa v181, v133 dst_sel:DWORD dst_unused:UNUSED_PAD src0_sel:WORD_1
	v_fma_f32 v134, v134, v134, v138
	v_fma_f32 v135, v135, v135, v139
	v_mul_f32_e32 v132, v179, v179
	v_add_f32_e32 v138, v134, v135
	v_add_f32_e32 v139, v135, v134
	v_cvt_f32_f16_e32 v180, v133
	v_fma_f32 v182, v178, v178, v132
	v_fma_f32 v183, v179, v179, v132
	v_cvt_f32_f16_sdwa v133, v130 dst_sel:DWORD dst_unused:UNUSED_PAD src0_sel:WORD_1
	v_cvt_f32_f16_e32 v132, v130
	v_cvt_f32_f16_sdwa v135, v131 dst_sel:DWORD dst_unused:UNUSED_PAD src0_sel:WORD_1
	v_cvt_f32_f16_e32 v134, v131
	v_mul_f32_e32 v130, v181, v181
	v_pk_add_f32 v[136:137], v[136:137], v[136:137] op_sel:[0,1] op_sel_hi:[1,0]
	v_fma_f32 v131, v181, v181, v130
	v_fma_f32 v130, v180, v180, v130
	v_mul_f32_e32 v184, v132, v132
	v_mul_f32_e32 v185, v133, v133
	v_mul_f32_e32 v186, v134, v134
	v_mul_f32_e32 v187, v135, v135
	v_mov_b32_e32 v137, v184
	v_mov_b32_e32 v139, v185
	v_mov_b32_e32 v183, v186
	v_mov_b32_e32 v131, v187
	v_add_f32_e32 v136, v136, v138
	v_add_f32_e32 v137, v137, v139
	v_add_f32_e32 v130, v182, v130
	v_add_f32_e32 v131, v183, v131
	s_waitcnt lgkmcnt(0)
	v_mul_f32_e32 v30, v26, v22
	v_mul_f32_e32 v31, v27, v23
	v_add_f32_e32 v130, v136, v130
	v_add_f32_e32 v131, v137, v131
	v_mul_f32_e32 v28, v24, v20
	v_mul_f32_e32 v29, v25, v21
	v_add_f32_e32 v130, v130, v131
	ds_read_b128 v[24:27], v153 offset:6144
	global_store_dwordx4 v[166:167], v[28:31], off offset:1024
	v_add_f32_dpp v130, v130, v130 quad_perm:[1,0,3,2] row_mask:0xf bank_mask:0xf bound_ctrl:1
	ds_read_b128 v[28:31], v153 offset:7168
	v_mul_f32_e32 v136, v148, v150
	v_mul_f32_e32 v137, v149, v150
	v_add_f32_dpp v130, v130, v130 quad_perm:[2,3,0,1] row_mask:0xf bank_mask:0xf bound_ctrl:1
	s_waitcnt lgkmcnt(1)
	v_mul_f32_e32 v156, v156, v26
	v_mul_f32_e32 v157, v157, v27
	v_mul_f32_e32 v154, v154, v24
	v_mul_f32_e32 v155, v155, v25
	v_add_f32_dpp v130, v130, v130 row_half_mirror row_mask:0xf bank_mask:0xf bound_ctrl:1
	global_store_dwordx4 v[166:167], v[154:157], off offset:2048
	s_nop 0
	v_add_f32_dpp v130, v130, v130 row_mirror row_mask:0xf bank_mask:0xf bound_ctrl:1
	s_nop 0
	v_readlane_b32 s17, v130, 16
	v_readlane_b32 s19, v130, 48
	v_readlane_b32 s0, v130, 0
	v_readlane_b32 s1, v130, 32
	v_mov_b32_e32 v130, s17
	v_mov_b32_e32 v131, s19
	v_add_f32_e32 v130, s0, v130
	v_add_f32_e32 v131, s1, v131
	s_nop 0
	v_add_f32_e32 v130, v130, v131
	v_fmamk_f32 v130, v130, 0x3a000000, v151
	v_mul_f32_e32 v131, 0x4f800000, v130
	v_cmp_gt_f32_e32 vcc, s18, v130
	s_nop 1
	v_cndmask_b32_e32 v138, v130, v131, vcc
	v_sqrt_f32_e32 v139, v138
	v_mul_f32_e32 v130, v146, v150
	v_mul_f32_e32 v131, v147, v150
	v_add_u32_e32 v146, -1, v139
	v_fma_f32 v147, -v146, v139, v138
	v_cmp_ge_f32_e64 s[0:1], 0, v147
	v_add_u32_e32 v147, 1, v139
	s_nop 0
	v_cndmask_b32_e64 v146, v139, v146, s[0:1]
	v_fma_f32 v139, -v147, v139, v138
	v_cmp_lt_f32_e64 s[0:1], 0, v139
	s_nop 1
	v_cndmask_b32_e64 v139, v146, v147, s[0:1]
	v_mul_f32_e32 v146, 0x37800000, v139
	v_cndmask_b32_e32 v139, v139, v146, vcc
	v_cmp_class_f32_e32 vcc, v138, v152
	s_nop 1
	v_cndmask_b32_e32 v146, v139, v138, vcc
	v_div_scale_f32 v147, s[0:1], v146, v146, 1.0
	v_rcp_f32_e32 v148, v147
	s_waitcnt lgkmcnt(0)
; #define GAS __attribute__((address_space(1)))
; #define LAS __attribute__((address_space(3)))
; #define FN_LOAD(dst, k_) do { const GAS v2u* xr_ = (const GAS v2u*)(X + (size_t)(nw + 2048 * (k_)) * D) + F.lane; \
;         _Pragma("unroll") for (int j = 0; j < 8; ++j) dst[j] = __builtin_nontemporal_load(xr_ + 64 * j); } while (0)
; __device__ __forceinline__ void final_norm_phase2(const Args& a, Frame& F) {
;     ...
;     FN_LOAD(r0, 0); FN_LOAD(r1, 1); FN_LOAD(r2, 2); FN_LOAD(r3, 3); FN_LOAD(r4, 4); FN_LOAD(r5, 5); FN_LOAD(r6, 6); FN_LOAD(r7, 7);
;     for (int q = F.tid; q < D / 4; q += NWAVES * 64) ((LAS f32x4*)GL)[q] = ((const GAS f32x4*)gain)[q];
;     asm volatile("s_waitcnt lgkmcnt(0)" ::: "memory"); __builtin_amdgcn_s_barrier(); asm volatile("" ::: "memory");
;     FN_FINISH(r0, 0); FN_FINISH(r1, 1); FN_FINISH(r2, 2); FN_FINISH(r3, 3); FN_FINISH(r4, 4); FN_FINISH(r5, 5); FN_FINISH(r6, 6); FN_FINISH(r7, 7);
	v_mul_f32_e32 v138, v136, v30
	v_mul_f32_e32 v139, v137, v31
	v_mul_f32_e32 v136, v130, v28
	v_mul_f32_e32 v137, v131, v29
	global_store_dwordx4 v[166:167], v[136:139], off offset:3072
	v_fma_f32 v130, -v147, v148, 1.0
	v_fmac_f32_e32 v148, v130, v148
	v_div_scale_f32 v130, vcc, 1.0, v146, 1.0
	v_mul_f32_e32 v131, v130, v148
	v_fma_f32 v136, -v147, v131, v130
	v_fmac_f32_e32 v131, v136, v148
	v_fma_f32 v130, -v147, v131, v130
	v_div_fmas_f32 v130, v130, v148, v131
	v_div_fixup_f32 v130, v130, v146, 1.0
	s_lshl_b64 s[0:1], s[14:15], 2
	s_add_u32 s0, s24, s0
	v_mul_f32_e32 v136, v158, v130
	v_mul_f32_e32 v137, v159, v130
	v_mul_f32_e32 v138, v160, v130
	v_mul_f32_e32 v139, v161, v130
	s_addc_u32 s1, s25, s1
	v_mul_f32_e32 v138, v2, v138
	v_mul_f32_e32 v139, v3, v139
	v_mul_f32_e32 v136, v0, v136
	v_mul_f32_e32 v137, v1, v137
	global_store_dwordx4 v48, v[136:139], s[0:1]
	v_lshl_add_u64 v[146:147], s[0:1], 0, v[48:49]
	v_cvt_f32_f16_sdwa v159, v123 dst_sel:DWORD dst_unused:UNUSED_PAD src0_sel:WORD_1
	v_mul_f32_e32 v136, v144, v130
	v_mul_f32_e32 v137, v145, v130
	v_mul_f32_e32 v138, v162, v130
	v_mul_f32_e32 v139, v163, v130
	v_mul_f32_e32 v136, v4, v136
	v_mul_f32_e32 v137, v5, v137
	v_mul_f32_e32 v138, v6, v138
	v_mul_f32_e32 v139, v7, v139
	global_store_dwordx4 v48, v[136:139], s[0:1] offset:1024
	v_add_co_u32_e32 v144, vcc, s16, v146
	s_nop 0
	v_mul_f32_e32 v136, v164, v130
	v_mul_f32_e32 v137, v165, v130
	v_mul_f32_e32 v138, v168, v130
	v_mul_f32_e32 v139, v169, v130
	v_mul_f32_e32 v136, v8, v136
	v_mul_f32_e32 v137, v9, v137
	v_mul_f32_e32 v138, v10, v138
	v_mul_f32_e32 v139, v11, v139
	global_store_dwordx4 v48, v[136:139], s[0:1] offset:2048
	v_addc_co_u32_e32 v145, vcc, 0, v147, vcc
	s_nop 0
	v_mul_f32_e32 v136, v170, v130
	v_mul_f32_e32 v137, v171, v130
	v_mul_f32_e32 v138, v172, v130
	v_mul_f32_e32 v139, v173, v130
	v_mul_f32_e32 v136, v12, v136
	v_mul_f32_e32 v137, v13, v137
	v_mul_f32_e32 v138, v14, v138
	v_mul_f32_e32 v139, v15, v139
	global_store_dwordx4 v48, v[136:139], s[0:1] offset:3072
	v_cvt_f32_f16_sdwa v147, v127 dst_sel:DWORD dst_unused:UNUSED_PAD src0_sel:WORD_1
	v_cvt_f32_f16_e32 v146, v127
	v_mul_f32_e32 v136, v174, v130
	v_mul_f32_e32 v137, v175, v130
	v_mul_f32_e32 v138, v176, v130
	v_mul_f32_e32 v139, v177, v130
	v_mul_f32_e32 v136, v16, v136
	v_mul_f32_e32 v137, v17, v137
	v_mul_f32_e32 v138, v18, v138
	v_mul_f32_e32 v139, v19, v139
	global_store_dwordx4 v[144:145], v[136:139], off
	v_mov_b32_e32 v155, v147
	v_cvt_f32_f16_e32 v158, v123
	v_mul_f32_e32 v136, v140, v130
	v_mul_f32_e32 v137, v141, v130
	v_mul_f32_e32 v138, v142, v130
	v_mul_f32_e32 v139, v143, v130
	v_cvt_f32_f16_sdwa v141, v128 dst_sel:DWORD dst_unused:UNUSED_PAD src0_sel:WORD_1
	v_cvt_f32_f16_sdwa v143, v129 dst_sel:DWORD dst_unused:UNUSED_PAD src0_sel:WORD_1
	v_cvt_f32_f16_e32 v142, v129
	v_cvt_f32_f16_sdwa v129, v126 dst_sel:DWORD dst_unused:UNUSED_PAD src0_sel:WORD_1
	v_cvt_f32_f16_e32 v140, v128
	v_cvt_f32_f16_e32 v128, v126
	v_mov_b32_e32 v148, v141
	v_mov_b32_e32 v149, v129
	v_mov_b32_e32 v126, v140
	v_mov_b32_e32 v127, v128
	v_mul_f32_e32 v148, v148, v148
	v_mul_f32_e32 v149, v149, v149
	v_mov_b32_e32 v154, v143
	v_fma_f32 v126, v126, v126, v148
	v_fma_f32 v127, v127, v127, v149
	v_mov_b32_e32 v148, v142
	v_mov_b32_e32 v149, v146
	v_mul_f32_e32 v154, v154, v154
	v_mul_f32_e32 v155, v155, v155
	v_cvt_f32_f16_sdwa v161, v120 dst_sel:DWORD dst_unused:UNUSED_PAD src0_sel:WORD_1
	v_fma_f32 v148, v148, v148, v154
	v_fma_f32 v149, v149, v149, v155
	v_cvt_f32_f16_sdwa v155, v125 dst_sel:DWORD dst_unused:UNUSED_PAD src0_sel:WORD_1
	v_add_f32_e32 v126, v126, v148
	v_add_f32_e32 v127, v127, v149
	v_cvt_f32_f16_sdwa v149, v124 dst_sel:DWORD dst_unused:UNUSED_PAD src0_sel:WORD_1
	v_cvt_f32_f16_e32 v148, v124
	v_cvt_f32_f16_e32 v154, v125
	v_mov_b32_e32 v157, v155
	v_mov_b32_e32 v156, v149
	v_mov_b32_e32 v124, v148
	v_mov_b32_e32 v125, v154
	v_mul_f32_e32 v156, v156, v156
	v_mul_f32_e32 v157, v157, v157
	v_cvt_f32_f16_e32 v160, v120
	v_fma_f32 v124, v124, v124, v156
	v_fma_f32 v125, v125, v125, v157
	v_cvt_f32_f16_sdwa v157, v122 dst_sel:DWORD dst_unused:UNUSED_PAD src0_sel:WORD_1
	v_cvt_f32_f16_e32 v156, v122
	v_cvt_f32_f16_sdwa v163, v121 dst_sel:DWORD dst_unused:UNUSED_PAD src0_sel:WORD_1
	v_cvt_f32_f16_e32 v162, v121
	v_mul_f32_e32 v122, v157, v157
	v_mul_f32_e32 v120, v159, v159
	v_pk_add_f32 v[126:127], v[126:127], v[126:127] op_sel:[0,1] op_sel_hi:[1,0]
	v_pk_add_f32 v[124:125], v[124:125], v[124:125] op_sel:[0,1] op_sel_hi:[1,0]
	v_fma_f32 v123, v157, v157, v122
	v_fma_f32 v122, v156, v156, v122
	v_fma_f32 v121, v159, v159, v120
	v_fma_f32 v120, v158, v158, v120
	v_mul_f32_e32 v164, v160, v160
	v_mul_f32_e32 v165, v161, v161
	v_mul_f32_e32 v166, v162, v162
	v_mul_f32_e32 v167, v163, v163
	v_mov_b32_e32 v127, v164
	v_mov_b32_e32 v125, v165
	v_mov_b32_e32 v123, v166
	v_mov_b32_e32 v121, v167
	v_add_f32_e32 v124, v126, v124
	v_add_f32_e32 v125, v127, v125
	v_add_f32_e32 v120, v122, v120
	v_add_f32_e32 v121, v123, v121
	v_cvt_f32_f16_sdwa v127, v119 dst_sel:DWORD dst_unused:UNUSED_PAD src0_sel:WORD_1
	v_add_f32_e32 v120, v124, v120
	v_add_f32_e32 v121, v125, v121
	v_cvt_f32_f16_sdwa v125, v118 dst_sel:DWORD dst_unused:UNUSED_PAD src0_sel:WORD_1
	v_cvt_f32_f16_e32 v124, v118
	v_cvt_f32_f16_e32 v126, v119
	v_cvt_f32_f16_sdwa v165, v116 dst_sel:DWORD dst_unused:UNUSED_PAD src0_sel:WORD_1
	v_cvt_f32_f16_e32 v164, v116
	v_mov_b32_e32 v122, v125
	v_mov_b32_e32 v123, v127
	v_mov_b32_e32 v118, v124
	v_mov_b32_e32 v119, v126
	v_mul_f32_e32 v122, v122, v122
	v_mul_f32_e32 v123, v123, v123
	v_cvt_f32_f16_sdwa v167, v117 dst_sel:DWORD dst_unused:UNUSED_PAD src0_sel:WORD_1
; #define GAS __attribute__((address_space(1)))
; #define LAS __attribute__((address_space(3)))
; #define FN_LOAD(dst, k_) do { const GAS v2u* xr_ = (const GAS v2u*)(X + (size_t)(nw + 2048 * (k_)) * D) + F.lane; \
;         _Pragma("unroll") for (int j = 0; j < 8; ++j) dst[j] = __builtin_nontemporal_load(xr_ + 64 * j); } while (0)
; __device__ __forceinline__ void final_norm_phase2(const Args& a, Frame& F) {
;     ...
;     FN_LOAD(r0, 0); FN_LOAD(r1, 1); FN_LOAD(r2, 2); FN_LOAD(r3, 3); FN_LOAD(r4, 4); FN_LOAD(r5, 5); FN_LOAD(r6, 6); FN_LOAD(r7, 7);
;     for (int q = F.tid; q < D / 4; q += NWAVES * 64) ((LAS f32x4*)GL)[q] = ((const GAS f32x4*)gain)[q];
;     asm volatile("s_waitcnt lgkmcnt(0)" ::: "memory"); __builtin_amdgcn_s_barrier(); asm volatile("" ::: "memory");
;     FN_FINISH(r0, 0); FN_FINISH(r1, 1); FN_FINISH(r2, 2); FN_FINISH(r3, 3); FN_FINISH(r4, 4); FN_FINISH(r5, 5); FN_FINISH(r6, 6); FN_FINISH(r7, 7);
	v_fma_f32 v118, v118, v118, v122
	v_fma_f32 v119, v119, v119, v123
	v_mul_f32_e32 v116, v165, v165
	v_add_f32_e32 v122, v118, v119
	v_add_f32_e32 v123, v119, v118
	v_cvt_f32_f16_e32 v166, v117
	v_fma_f32 v168, v164, v164, v116
	v_fma_f32 v169, v165, v165, v116
	v_cvt_f32_f16_sdwa v117, v114 dst_sel:DWORD dst_unused:UNUSED_PAD src0_sel:WORD_1
	v_cvt_f32_f16_e32 v116, v114
	v_cvt_f32_f16_sdwa v119, v115 dst_sel:DWORD dst_unused:UNUSED_PAD src0_sel:WORD_1
	v_cvt_f32_f16_e32 v118, v115
	v_mul_f32_e32 v114, v167, v167
	v_pk_add_f32 v[120:121], v[120:121], v[120:121] op_sel:[0,1] op_sel_hi:[1,0]
	v_fma_f32 v115, v167, v167, v114
	v_fma_f32 v114, v166, v166, v114
	v_mul_f32_e32 v170, v116, v116
	v_mul_f32_e32 v171, v117, v117
	v_mul_f32_e32 v172, v118, v118
	v_mul_f32_e32 v173, v119, v119
	v_mov_b32_e32 v121, v170
	v_mov_b32_e32 v123, v171
	v_mov_b32_e32 v169, v172
	v_mov_b32_e32 v115, v173
	v_add_f32_e32 v120, v120, v122
	v_add_f32_e32 v121, v121, v123
	v_add_f32_e32 v114, v168, v114
	v_add_f32_e32 v115, v169, v115
	v_mul_f32_e32 v138, v22, v138
	v_mul_f32_e32 v139, v23, v139
	v_add_f32_e32 v114, v120, v114
	v_add_f32_e32 v115, v121, v115
	v_mul_f32_e32 v136, v20, v136
	v_mul_f32_e32 v137, v21, v137
	v_add_f32_e32 v114, v114, v115
	global_store_dwordx4 v[144:145], v[136:139], off offset:1024
	v_mul_f32_e32 v120, v134, v130
	v_mul_f32_e32 v121, v135, v130
	v_add_f32_dpp v114, v114, v114 quad_perm:[1,0,3,2] row_mask:0xf bank_mask:0xf bound_ctrl:1
	v_mul_f32_e32 v136, v178, v130
	v_mul_f32_e32 v137, v179, v130
	v_mul_f32_e32 v138, v180, v130
	v_mul_f32_e32 v139, v181, v130
	v_add_f32_dpp v114, v114, v114 quad_perm:[2,3,0,1] row_mask:0xf bank_mask:0xf bound_ctrl:1
	v_mul_f32_e32 v138, v26, v138
	v_mul_f32_e32 v139, v27, v139
	v_mul_f32_e32 v136, v24, v136
	v_mul_f32_e32 v137, v25, v137
	v_add_f32_dpp v114, v114, v114 row_half_mirror row_mask:0xf bank_mask:0xf bound_ctrl:1
	global_store_dwordx4 v[144:145], v[136:139], off offset:2048
	s_nop 0
	v_add_f32_dpp v114, v114, v114 row_mirror row_mask:0xf bank_mask:0xf bound_ctrl:1
	v_cvt_f32_f16_sdwa v139, v107 dst_sel:DWORD dst_unused:UNUSED_PAD src0_sel:WORD_1
	v_readlane_b32 s14, v114, 16
	v_readlane_b32 s15, v114, 48
	v_readlane_b32 s0, v114, 0
	v_readlane_b32 s1, v114, 32
	v_mov_b32_e32 v114, s14
	v_mov_b32_e32 v115, s15
	v_add_f32_e32 v114, s0, v114
	v_add_f32_e32 v115, s1, v115
	v_cvt_f32_f16_e32 v138, v107
	v_add_f32_e32 v114, v114, v115
	v_fmamk_f32 v114, v114, 0x3a000000, v151
	v_mul_f32_e32 v115, 0x4f800000, v114
	v_cmp_gt_f32_e32 vcc, s18, v114
	s_nop 1
	v_cndmask_b32_e32 v122, v114, v115, vcc
	v_sqrt_f32_e32 v123, v122
	v_mul_f32_e32 v114, v132, v130
	v_mul_f32_e32 v115, v133, v130
	v_add_u32_e32 v130, -1, v123
	v_fma_f32 v131, -v130, v123, v122
	v_cmp_ge_f32_e64 s[0:1], 0, v131
	v_add_u32_e32 v131, 1, v123
	s_nop 0
	v_cndmask_b32_e64 v130, v123, v130, s[0:1]
	v_fma_f32 v123, -v131, v123, v122
	v_cmp_lt_f32_e64 s[0:1], 0, v123
	s_nop 1
	v_cndmask_b32_e64 v123, v130, v131, s[0:1]
	v_mul_f32_e32 v130, 0x37800000, v123
	v_cndmask_b32_e32 v123, v123, v130, vcc
	v_cmp_class_f32_e32 vcc, v122, v152
	s_nop 1
	v_cndmask_b32_e32 v130, v123, v122, vcc
	v_div_scale_f32 v131, s[0:1], v130, v130, 1.0
	v_rcp_f32_e32 v132, v131
	v_mul_f32_e32 v122, v30, v120
	v_mul_f32_e32 v123, v31, v121
	v_mul_f32_e32 v120, v28, v114
	v_mul_f32_e32 v121, v29, v115
	global_store_dwordx4 v[144:145], v[120:123], off offset:3072
	v_fma_f32 v114, -v131, v132, 1.0
	v_fmac_f32_e32 v132, v114, v132
	v_div_scale_f32 v114, vcc, 1.0, v130, 1.0
	v_mul_f32_e32 v115, v114, v132
	v_fma_f32 v120, -v131, v115, v114
	v_fmac_f32_e32 v115, v120, v132
	v_fma_f32 v114, -v131, v115, v114
	v_div_fmas_f32 v114, v114, v132, v115
	v_div_fixup_f32 v114, v114, v130, 1.0
	s_lshl_b64 s[0:1], s[12:13], 2
	s_add_u32 s0, s24, s0
	v_mul_f32_e32 v120, v140, v114
	v_mul_f32_e32 v121, v141, v114
	v_mul_f32_e32 v122, v142, v114
	v_mul_f32_e32 v123, v143, v114
	s_addc_u32 s1, s25, s1
	v_mul_f32_e32 v122, v2, v122
	v_mul_f32_e32 v123, v3, v123
	v_mul_f32_e32 v120, v0, v120
	v_mul_f32_e32 v121, v1, v121
	global_store_dwordx4 v48, v[120:123], s[0:1]
	v_lshl_add_u64 v[130:131], s[0:1], 0, v[48:49]
	v_cvt_f32_f16_sdwa v141, v104 dst_sel:DWORD dst_unused:UNUSED_PAD src0_sel:WORD_1
	v_mul_f32_e32 v120, v128, v114
	v_mul_f32_e32 v121, v129, v114
	v_mul_f32_e32 v122, v146, v114
	v_mul_f32_e32 v123, v147, v114
	v_mul_f32_e32 v120, v4, v120
	v_mul_f32_e32 v121, v5, v121
	v_mul_f32_e32 v122, v6, v122
	v_mul_f32_e32 v123, v7, v123
	global_store_dwordx4 v48, v[120:123], s[0:1] offset:1024
	v_add_co_u32_e32 v128, vcc, s16, v130
	s_nop 0
	v_mul_f32_e32 v120, v148, v114
	v_mul_f32_e32 v121, v149, v114
	v_mul_f32_e32 v122, v154, v114
	v_mul_f32_e32 v123, v155, v114
	v_mul_f32_e32 v120, v8, v120
	v_mul_f32_e32 v121, v9, v121
	v_mul_f32_e32 v122, v10, v122
	v_mul_f32_e32 v123, v11, v123
	global_store_dwordx4 v48, v[120:123], s[0:1] offset:2048
	v_addc_co_u32_e32 v129, vcc, 0, v131, vcc
	s_nop 0
	v_mul_f32_e32 v120, v156, v114
	v_mul_f32_e32 v121, v157, v114
	v_mul_f32_e32 v122, v158, v114
	v_mul_f32_e32 v123, v159, v114
	v_mul_f32_e32 v120, v12, v120
	v_mul_f32_e32 v121, v13, v121
	v_mul_f32_e32 v122, v14, v122
	v_mul_f32_e32 v123, v15, v123
	global_store_dwordx4 v48, v[120:123], s[0:1] offset:3072
	v_cvt_f32_f16_sdwa v131, v111 dst_sel:DWORD dst_unused:UNUSED_PAD src0_sel:WORD_1
	v_cvt_f32_f16_e32 v130, v111
	v_mul_f32_e32 v120, v160, v114
	v_mul_f32_e32 v121, v161, v114
	v_mul_f32_e32 v122, v162, v114
	v_mul_f32_e32 v123, v163, v114
	v_mul_f32_e32 v120, v16, v120
	v_mul_f32_e32 v121, v17, v121
	v_mul_f32_e32 v122, v18, v122
	v_mul_f32_e32 v123, v19, v123
; #define GAS __attribute__((address_space(1)))
; #define LAS __attribute__((address_space(3)))
; #define FN_LOAD(dst, k_) do { const GAS v2u* xr_ = (const GAS v2u*)(X + (size_t)(nw + 2048 * (k_)) * D) + F.lane; \
;         _Pragma("unroll") for (int j = 0; j < 8; ++j) dst[j] = __builtin_nontemporal_load(xr_ + 64 * j); } while (0)
; __device__ __forceinline__ void final_norm_phase2(const Args& a, Frame& F) {
;     ...
;     FN_LOAD(r0, 0); FN_LOAD(r1, 1); FN_LOAD(r2, 2); FN_LOAD(r3, 3); FN_LOAD(r4, 4); FN_LOAD(r5, 5); FN_LOAD(r6, 6); FN_LOAD(r7, 7);
;     for (int q = F.tid; q < D / 4; q += NWAVES * 64) ((LAS f32x4*)GL)[q] = ((const GAS f32x4*)gain)[q];
;     asm volatile("s_waitcnt lgkmcnt(0)" ::: "memory"); __builtin_amdgcn_s_barrier(); asm volatile("" ::: "memory");
;     FN_FINISH(r0, 0); FN_FINISH(r1, 1); FN_FINISH(r2, 2); FN_FINISH(r3, 3); FN_FINISH(r4, 4); FN_FINISH(r5, 5); FN_FINISH(r6, 6); FN_FINISH(r7, 7);
	global_store_dwordx4 v[128:129], v[120:123], off
	v_mov_b32_e32 v135, v131
	v_cvt_f32_f16_e32 v140, v104
	v_mul_f32_e32 v120, v124, v114
	v_mul_f32_e32 v121, v125, v114
	v_mul_f32_e32 v122, v126, v114
	v_mul_f32_e32 v123, v127, v114
	v_cvt_f32_f16_sdwa v125, v112 dst_sel:DWORD dst_unused:UNUSED_PAD src0_sel:WORD_1
	v_cvt_f32_f16_sdwa v127, v113 dst_sel:DWORD dst_unused:UNUSED_PAD src0_sel:WORD_1
	v_cvt_f32_f16_e32 v126, v113
	v_cvt_f32_f16_sdwa v113, v110 dst_sel:DWORD dst_unused:UNUSED_PAD src0_sel:WORD_1
	v_cvt_f32_f16_e32 v124, v112
	v_cvt_f32_f16_e32 v112, v110
	v_mov_b32_e32 v132, v125
	v_mov_b32_e32 v133, v113
	v_mov_b32_e32 v110, v124
	v_mov_b32_e32 v111, v112
	v_mul_f32_e32 v132, v132, v132
	v_mul_f32_e32 v133, v133, v133
	v_mov_b32_e32 v134, v127
	v_fma_f32 v110, v110, v110, v132
	v_fma_f32 v111, v111, v111, v133
	v_mov_b32_e32 v132, v126
	v_mov_b32_e32 v133, v130
	v_mul_f32_e32 v134, v134, v134
	v_mul_f32_e32 v135, v135, v135
	v_cvt_f32_f16_sdwa v143, v105 dst_sel:DWORD dst_unused:UNUSED_PAD src0_sel:WORD_1
	v_fma_f32 v132, v132, v132, v134
	v_fma_f32 v133, v133, v133, v135
	v_cvt_f32_f16_sdwa v135, v109 dst_sel:DWORD dst_unused:UNUSED_PAD src0_sel:WORD_1
	v_add_f32_e32 v110, v110, v132
	v_add_f32_e32 v111, v111, v133
	v_cvt_f32_f16_sdwa v133, v108 dst_sel:DWORD dst_unused:UNUSED_PAD src0_sel:WORD_1
	v_cvt_f32_f16_e32 v132, v108
	v_cvt_f32_f16_e32 v134, v109
	v_mov_b32_e32 v137, v135
	v_mov_b32_e32 v136, v133
	v_mov_b32_e32 v108, v132
	v_mov_b32_e32 v109, v134
	v_mul_f32_e32 v136, v136, v136
	v_mul_f32_e32 v137, v137, v137
	v_cvt_f32_f16_e32 v142, v105
	v_fma_f32 v108, v108, v108, v136
	v_fma_f32 v109, v109, v109, v137
	v_cvt_f32_f16_sdwa v137, v106 dst_sel:DWORD dst_unused:UNUSED_PAD src0_sel:WORD_1
	v_cvt_f32_f16_e32 v136, v106
	v_mul_f32_e32 v104, v139, v139
	v_pk_add_f32 v[110:111], v[110:111], v[110:111] op_sel:[0,1] op_sel_hi:[1,0]
	v_mul_f32_e32 v106, v137, v137
	v_pk_add_f32 v[108:109], v[108:109], v[108:109] op_sel:[0,1] op_sel_hi:[1,0]
	v_fma_f32 v107, v137, v137, v106
	v_fma_f32 v106, v136, v136, v106
	v_fma_f32 v105, v139, v139, v104
	v_fma_f32 v104, v138, v138, v104
	v_mul_f32_e32 v144, v140, v140
	v_mul_f32_e32 v145, v141, v141
	v_mul_f32_e32 v146, v142, v142
	v_mul_f32_e32 v147, v143, v143
	v_mov_b32_e32 v111, v144
	v_mov_b32_e32 v109, v145
	v_mov_b32_e32 v107, v146
	v_mov_b32_e32 v105, v147
	v_add_f32_e32 v108, v110, v108
	v_add_f32_e32 v109, v111, v109
	v_add_f32_e32 v104, v106, v104
	v_add_f32_e32 v105, v107, v105
	v_cvt_f32_f16_sdwa v111, v103 dst_sel:DWORD dst_unused:UNUSED_PAD src0_sel:WORD_1
	v_add_f32_e32 v104, v108, v104
	v_add_f32_e32 v105, v109, v105
	v_cvt_f32_f16_sdwa v109, v102 dst_sel:DWORD dst_unused:UNUSED_PAD src0_sel:WORD_1
	v_cvt_f32_f16_e32 v108, v102
	v_cvt_f32_f16_e32 v110, v103
	v_cvt_f32_f16_sdwa v145, v100 dst_sel:DWORD dst_unused:UNUSED_PAD src0_sel:WORD_1
	v_cvt_f32_f16_e32 v144, v100
	v_mov_b32_e32 v106, v109
	v_mov_b32_e32 v107, v111
	v_mov_b32_e32 v102, v108
	v_mov_b32_e32 v103, v110
	v_mul_f32_e32 v106, v106, v106
	v_mul_f32_e32 v107, v107, v107
	v_cvt_f32_f16_sdwa v147, v101 dst_sel:DWORD dst_unused:UNUSED_PAD src0_sel:WORD_1
	v_fma_f32 v102, v102, v102, v106
	v_fma_f32 v103, v103, v103, v107
	v_mul_f32_e32 v100, v145, v145
	v_add_f32_e32 v106, v102, v103
	v_add_f32_e32 v107, v103, v102
	v_cvt_f32_f16_e32 v146, v101
	v_fma_f32 v148, v144, v144, v100
	v_fma_f32 v149, v145, v145, v100
	v_cvt_f32_f16_sdwa v101, v98 dst_sel:DWORD dst_unused:UNUSED_PAD src0_sel:WORD_1
	v_cvt_f32_f16_e32 v100, v98
	v_cvt_f32_f16_sdwa v103, v99 dst_sel:DWORD dst_unused:UNUSED_PAD src0_sel:WORD_1
	v_cvt_f32_f16_e32 v102, v99
	v_mul_f32_e32 v98, v147, v147
	v_pk_add_f32 v[104:105], v[104:105], v[104:105] op_sel:[0,1] op_sel_hi:[1,0]
	v_fma_f32 v99, v147, v147, v98
	v_fma_f32 v98, v146, v146, v98
	v_mul_f32_e32 v154, v100, v100
	v_mul_f32_e32 v155, v101, v101
	v_mul_f32_e32 v156, v102, v102
	v_mul_f32_e32 v157, v103, v103
	v_mov_b32_e32 v105, v154
	v_mov_b32_e32 v107, v155
	v_mov_b32_e32 v149, v156
	v_mov_b32_e32 v99, v157
	v_add_f32_e32 v104, v104, v106
	v_add_f32_e32 v105, v105, v107
	v_add_f32_e32 v98, v148, v98
	v_add_f32_e32 v99, v149, v99
	v_mul_f32_e32 v122, v22, v122
	v_mul_f32_e32 v123, v23, v123
	v_add_f32_e32 v98, v104, v98
	v_add_f32_e32 v99, v105, v99
	v_mul_f32_e32 v120, v20, v120
	v_mul_f32_e32 v121, v21, v121
	v_add_f32_e32 v98, v98, v99
	global_store_dwordx4 v[128:129], v[120:123], off offset:1024
	v_mul_f32_e32 v104, v118, v114
	v_mul_f32_e32 v105, v119, v114
	v_add_f32_dpp v98, v98, v98 quad_perm:[1,0,3,2] row_mask:0xf bank_mask:0xf bound_ctrl:1
	v_mul_f32_e32 v120, v164, v114
	v_mul_f32_e32 v121, v165, v114
	v_mul_f32_e32 v122, v166, v114
	v_mul_f32_e32 v123, v167, v114
	v_add_f32_dpp v98, v98, v98 quad_perm:[2,3,0,1] row_mask:0xf bank_mask:0xf bound_ctrl:1
	v_mul_f32_e32 v122, v26, v122
	v_mul_f32_e32 v123, v27, v123
	v_mul_f32_e32 v120, v24, v120
	v_mul_f32_e32 v121, v25, v121
	v_add_f32_dpp v98, v98, v98 row_half_mirror row_mask:0xf bank_mask:0xf bound_ctrl:1
	global_store_dwordx4 v[128:129], v[120:123], off offset:2048
	s_nop 0
	v_add_f32_dpp v98, v98, v98 row_mirror row_mask:0xf bank_mask:0xf bound_ctrl:1
	v_cvt_f32_f16_sdwa v123, v91 dst_sel:DWORD dst_unused:UNUSED_PAD src0_sel:WORD_1
	v_readlane_b32 s12, v98, 16
	v_readlane_b32 s13, v98, 48
	v_readlane_b32 s0, v98, 0
	v_readlane_b32 s1, v98, 32
	v_mov_b32_e32 v98, s12
	v_mov_b32_e32 v99, s13
	v_add_f32_e32 v98, s0, v98
	v_add_f32_e32 v99, s1, v99
	v_cvt_f32_f16_e32 v122, v91
	v_add_f32_e32 v98, v98, v99
	v_fmamk_f32 v98, v98, 0x3a000000, v151
	v_mul_f32_e32 v99, 0x4f800000, v98
	v_cmp_gt_f32_e32 vcc, s18, v98
	s_nop 1
; #define GAS __attribute__((address_space(1)))
; #define LAS __attribute__((address_space(3)))
; #define FN_LOAD(dst, k_) do { const GAS v2u* xr_ = (const GAS v2u*)(X + (size_t)(nw + 2048 * (k_)) * D) + F.lane; \
;         _Pragma("unroll") for (int j = 0; j < 8; ++j) dst[j] = __builtin_nontemporal_load(xr_ + 64 * j); } while (0)
; __device__ __forceinline__ void final_norm_phase2(const Args& a, Frame& F) {
;     ...
;     FN_LOAD(r0, 0); FN_LOAD(r1, 1); FN_LOAD(r2, 2); FN_LOAD(r3, 3); FN_LOAD(r4, 4); FN_LOAD(r5, 5); FN_LOAD(r6, 6); FN_LOAD(r7, 7);
;     for (int q = F.tid; q < D / 4; q += NWAVES * 64) ((LAS f32x4*)GL)[q] = ((const GAS f32x4*)gain)[q];
;     asm volatile("s_waitcnt lgkmcnt(0)" ::: "memory"); __builtin_amdgcn_s_barrier(); asm volatile("" ::: "memory");
;     FN_FINISH(r0, 0); FN_FINISH(r1, 1); FN_FINISH(r2, 2); FN_FINISH(r3, 3); FN_FINISH(r4, 4); FN_FINISH(r5, 5); FN_FINISH(r6, 6); FN_FINISH(r7, 7);
	v_cndmask_b32_e32 v106, v98, v99, vcc
	v_sqrt_f32_e32 v107, v106
	v_mul_f32_e32 v98, v116, v114
	v_mul_f32_e32 v99, v117, v114
	v_add_u32_e32 v114, -1, v107
	v_fma_f32 v115, -v114, v107, v106
	v_cmp_ge_f32_e64 s[0:1], 0, v115
	v_add_u32_e32 v115, 1, v107
	s_nop 0
	v_cndmask_b32_e64 v114, v107, v114, s[0:1]
	v_fma_f32 v107, -v115, v107, v106
	v_cmp_lt_f32_e64 s[0:1], 0, v107
	s_nop 1
	v_cndmask_b32_e64 v107, v114, v115, s[0:1]
	v_mul_f32_e32 v114, 0x37800000, v107
	v_cndmask_b32_e32 v107, v107, v114, vcc
	v_cmp_class_f32_e32 vcc, v106, v152
	s_nop 1
	v_cndmask_b32_e32 v114, v107, v106, vcc
	v_div_scale_f32 v115, s[0:1], v114, v114, 1.0
	v_rcp_f32_e32 v116, v115
	v_mul_f32_e32 v106, v30, v104
	v_mul_f32_e32 v107, v31, v105
	v_mul_f32_e32 v104, v28, v98
	v_mul_f32_e32 v105, v29, v99
	global_store_dwordx4 v[128:129], v[104:107], off offset:3072
	v_fma_f32 v98, -v115, v116, 1.0
	v_fmac_f32_e32 v116, v98, v116
	v_div_scale_f32 v98, vcc, 1.0, v114, 1.0
	v_mul_f32_e32 v99, v98, v116
	v_fma_f32 v104, -v115, v99, v98
	v_fmac_f32_e32 v99, v104, v116
	v_fma_f32 v98, -v115, v99, v98
	v_div_fmas_f32 v98, v98, v116, v99
	v_div_fixup_f32 v98, v98, v114, 1.0
	s_lshl_b64 s[0:1], s[10:11], 2
	s_add_u32 s0, s24, s0
	v_mul_f32_e32 v104, v124, v98
	v_mul_f32_e32 v105, v125, v98
	v_mul_f32_e32 v106, v126, v98
	v_mul_f32_e32 v107, v127, v98
	s_addc_u32 s1, s25, s1
	v_mul_f32_e32 v106, v2, v106
	v_mul_f32_e32 v107, v3, v107
	v_mul_f32_e32 v104, v0, v104
	v_mul_f32_e32 v105, v1, v105
	global_store_dwordx4 v48, v[104:107], s[0:1]
	v_lshl_add_u64 v[114:115], s[0:1], 0, v[48:49]
	v_cvt_f32_f16_sdwa v125, v88 dst_sel:DWORD dst_unused:UNUSED_PAD src0_sel:WORD_1
	v_mul_f32_e32 v104, v112, v98
	v_mul_f32_e32 v105, v113, v98
	v_mul_f32_e32 v106, v130, v98
	v_mul_f32_e32 v107, v131, v98
	v_mul_f32_e32 v104, v4, v104
	v_mul_f32_e32 v105, v5, v105
	v_mul_f32_e32 v106, v6, v106
	v_mul_f32_e32 v107, v7, v107
	global_store_dwordx4 v48, v[104:107], s[0:1] offset:1024
	v_add_co_u32_e32 v112, vcc, s16, v114
	s_nop 0
	v_mul_f32_e32 v104, v132, v98
	v_mul_f32_e32 v105, v133, v98
	v_mul_f32_e32 v106, v134, v98
	v_mul_f32_e32 v107, v135, v98
	v_mul_f32_e32 v104, v8, v104
	v_mul_f32_e32 v105, v9, v105
	v_mul_f32_e32 v106, v10, v106
	v_mul_f32_e32 v107, v11, v107
	global_store_dwordx4 v48, v[104:107], s[0:1] offset:2048
	v_addc_co_u32_e32 v113, vcc, 0, v115, vcc
	s_nop 0
	v_mul_f32_e32 v104, v136, v98
	v_mul_f32_e32 v105, v137, v98
	v_mul_f32_e32 v106, v138, v98
	v_mul_f32_e32 v107, v139, v98
	v_mul_f32_e32 v104, v12, v104
	v_mul_f32_e32 v105, v13, v105
	v_mul_f32_e32 v106, v14, v106
	v_mul_f32_e32 v107, v15, v107
	global_store_dwordx4 v48, v[104:107], s[0:1] offset:3072
	v_cvt_f32_f16_sdwa v115, v95 dst_sel:DWORD dst_unused:UNUSED_PAD src0_sel:WORD_1
	v_cvt_f32_f16_e32 v114, v95
	v_mul_f32_e32 v104, v140, v98
	v_mul_f32_e32 v105, v141, v98
	v_mul_f32_e32 v106, v142, v98
	v_mul_f32_e32 v107, v143, v98
	v_mul_f32_e32 v104, v16, v104
	v_mul_f32_e32 v105, v17, v105
	v_mul_f32_e32 v106, v18, v106
	v_mul_f32_e32 v107, v19, v107
	global_store_dwordx4 v[112:113], v[104:107], off
	v_mov_b32_e32 v119, v115
	v_cvt_f32_f16_e32 v124, v88
	v_mul_f32_e32 v104, v108, v98
	v_mul_f32_e32 v105, v109, v98
	v_mul_f32_e32 v106, v110, v98
	v_mul_f32_e32 v107, v111, v98
	v_cvt_f32_f16_sdwa v109, v96 dst_sel:DWORD dst_unused:UNUSED_PAD src0_sel:WORD_1
	v_cvt_f32_f16_sdwa v111, v97 dst_sel:DWORD dst_unused:UNUSED_PAD src0_sel:WORD_1
	v_cvt_f32_f16_e32 v110, v97
	v_cvt_f32_f16_sdwa v97, v94 dst_sel:DWORD dst_unused:UNUSED_PAD src0_sel:WORD_1
	v_cvt_f32_f16_e32 v108, v96
	v_cvt_f32_f16_e32 v96, v94
	v_mov_b32_e32 v116, v109
	v_mov_b32_e32 v117, v97
	v_mov_b32_e32 v94, v108
	v_mov_b32_e32 v95, v96
	v_mul_f32_e32 v116, v116, v116
	v_mul_f32_e32 v117, v117, v117
	v_mov_b32_e32 v118, v111
	v_fma_f32 v94, v94, v94, v116
	v_fma_f32 v95, v95, v95, v117
	v_mov_b32_e32 v116, v110
	v_mov_b32_e32 v117, v114
	v_mul_f32_e32 v118, v118, v118
	v_mul_f32_e32 v119, v119, v119
	v_cvt_f32_f16_sdwa v127, v89 dst_sel:DWORD dst_unused:UNUSED_PAD src0_sel:WORD_1
	v_fma_f32 v116, v116, v116, v118
	v_fma_f32 v117, v117, v117, v119
	v_cvt_f32_f16_sdwa v119, v93 dst_sel:DWORD dst_unused:UNUSED_PAD src0_sel:WORD_1
	v_add_f32_e32 v94, v94, v116
	v_add_f32_e32 v95, v95, v117
	v_cvt_f32_f16_sdwa v117, v92 dst_sel:DWORD dst_unused:UNUSED_PAD src0_sel:WORD_1
	v_cvt_f32_f16_e32 v116, v92
	v_cvt_f32_f16_e32 v118, v93
	v_mov_b32_e32 v121, v119
	v_mov_b32_e32 v120, v117
	v_mov_b32_e32 v92, v116
	v_mov_b32_e32 v93, v118
	v_mul_f32_e32 v120, v120, v120
	v_mul_f32_e32 v121, v121, v121
	v_cvt_f32_f16_e32 v126, v89
	v_fma_f32 v92, v92, v92, v120
	v_fma_f32 v93, v93, v93, v121
	v_cvt_f32_f16_sdwa v121, v90 dst_sel:DWORD dst_unused:UNUSED_PAD src0_sel:WORD_1
	v_cvt_f32_f16_e32 v120, v90
	v_mul_f32_e32 v88, v123, v123
	v_pk_add_f32 v[94:95], v[94:95], v[94:95] op_sel:[0,1] op_sel_hi:[1,0]
	v_mul_f32_e32 v90, v121, v121
	v_pk_add_f32 v[92:93], v[92:93], v[92:93] op_sel:[0,1] op_sel_hi:[1,0]
	v_fma_f32 v91, v121, v121, v90
	v_fma_f32 v90, v120, v120, v90
	v_fma_f32 v89, v123, v123, v88
	v_fma_f32 v88, v122, v122, v88
	v_mul_f32_e32 v128, v124, v124
	v_mul_f32_e32 v129, v125, v125
	v_mul_f32_e32 v130, v126, v126
	v_mul_f32_e32 v131, v127, v127
	v_mov_b32_e32 v95, v128
	v_mov_b32_e32 v93, v129
	v_mov_b32_e32 v91, v130
	v_mov_b32_e32 v89, v131
	v_add_f32_e32 v92, v94, v92
	v_add_f32_e32 v93, v95, v93
	v_add_f32_e32 v88, v90, v88
	v_add_f32_e32 v89, v91, v89
	v_cvt_f32_f16_sdwa v95, v87 dst_sel:DWORD dst_unused:UNUSED_PAD src0_sel:WORD_1
	v_add_f32_e32 v88, v92, v88
	v_add_f32_e32 v89, v93, v89
	v_cvt_f32_f16_sdwa v93, v86 dst_sel:DWORD dst_unused:UNUSED_PAD src0_sel:WORD_1
; #define GAS __attribute__((address_space(1)))
; #define LAS __attribute__((address_space(3)))
; #define FN_LOAD(dst, k_) do { const GAS v2u* xr_ = (const GAS v2u*)(X + (size_t)(nw + 2048 * (k_)) * D) + F.lane; \
;         _Pragma("unroll") for (int j = 0; j < 8; ++j) dst[j] = __builtin_nontemporal_load(xr_ + 64 * j); } while (0)
; __device__ __forceinline__ void final_norm_phase2(const Args& a, Frame& F) {
;     ...
;     FN_LOAD(r0, 0); FN_LOAD(r1, 1); FN_LOAD(r2, 2); FN_LOAD(r3, 3); FN_LOAD(r4, 4); FN_LOAD(r5, 5); FN_LOAD(r6, 6); FN_LOAD(r7, 7);
;     for (int q = F.tid; q < D / 4; q += NWAVES * 64) ((LAS f32x4*)GL)[q] = ((const GAS f32x4*)gain)[q];
;     asm volatile("s_waitcnt lgkmcnt(0)" ::: "memory"); __builtin_amdgcn_s_barrier(); asm volatile("" ::: "memory");
;     FN_FINISH(r0, 0); FN_FINISH(r1, 1); FN_FINISH(r2, 2); FN_FINISH(r3, 3); FN_FINISH(r4, 4); FN_FINISH(r5, 5); FN_FINISH(r6, 6); FN_FINISH(r7, 7);
	v_cvt_f32_f16_e32 v92, v86
	v_cvt_f32_f16_e32 v94, v87
	v_cvt_f32_f16_sdwa v129, v84 dst_sel:DWORD dst_unused:UNUSED_PAD src0_sel:WORD_1
	v_cvt_f32_f16_e32 v128, v84
	v_mov_b32_e32 v90, v93
	v_mov_b32_e32 v91, v95
	v_mov_b32_e32 v86, v92
	v_mov_b32_e32 v87, v94
	v_mul_f32_e32 v90, v90, v90
	v_mul_f32_e32 v91, v91, v91
	v_cvt_f32_f16_sdwa v131, v85 dst_sel:DWORD dst_unused:UNUSED_PAD src0_sel:WORD_1
	v_fma_f32 v86, v86, v86, v90
	v_fma_f32 v87, v87, v87, v91
	v_mul_f32_e32 v84, v129, v129
	v_add_f32_e32 v90, v86, v87
	v_add_f32_e32 v91, v87, v86
	v_cvt_f32_f16_e32 v130, v85
	v_fma_f32 v132, v128, v128, v84
	v_fma_f32 v133, v129, v129, v84
	v_cvt_f32_f16_sdwa v85, v82 dst_sel:DWORD dst_unused:UNUSED_PAD src0_sel:WORD_1
	v_cvt_f32_f16_e32 v84, v82
	v_cvt_f32_f16_sdwa v87, v83 dst_sel:DWORD dst_unused:UNUSED_PAD src0_sel:WORD_1
	v_cvt_f32_f16_e32 v86, v83
	v_mul_f32_e32 v82, v131, v131
	v_pk_add_f32 v[88:89], v[88:89], v[88:89] op_sel:[0,1] op_sel_hi:[1,0]
	v_fma_f32 v83, v131, v131, v82
	v_fma_f32 v82, v130, v130, v82
	v_mul_f32_e32 v134, v84, v84
	v_mul_f32_e32 v135, v85, v85
	v_mul_f32_e32 v136, v86, v86
	v_mul_f32_e32 v137, v87, v87
	v_mov_b32_e32 v89, v134
	v_mov_b32_e32 v91, v135
	v_mov_b32_e32 v133, v136
	v_mov_b32_e32 v83, v137
	v_add_f32_e32 v88, v88, v90
	v_add_f32_e32 v89, v89, v91
	v_add_f32_e32 v82, v132, v82
	v_add_f32_e32 v83, v133, v83
	v_mul_f32_e32 v106, v22, v106
	v_mul_f32_e32 v107, v23, v107
	v_add_f32_e32 v82, v88, v82
	v_add_f32_e32 v83, v89, v83
	v_mul_f32_e32 v104, v20, v104
	v_mul_f32_e32 v105, v21, v105
	v_add_f32_e32 v82, v82, v83
	global_store_dwordx4 v[112:113], v[104:107], off offset:1024
	v_mul_f32_e32 v88, v102, v98
	v_mul_f32_e32 v89, v103, v98
	v_add_f32_dpp v82, v82, v82 quad_perm:[1,0,3,2] row_mask:0xf bank_mask:0xf bound_ctrl:1
	v_mul_f32_e32 v104, v144, v98
	v_mul_f32_e32 v105, v145, v98
	v_mul_f32_e32 v106, v146, v98
	v_mul_f32_e32 v107, v147, v98
	v_add_f32_dpp v82, v82, v82 quad_perm:[2,3,0,1] row_mask:0xf bank_mask:0xf bound_ctrl:1
	v_mul_f32_e32 v106, v26, v106
	v_mul_f32_e32 v107, v27, v107
	v_mul_f32_e32 v104, v24, v104
	v_mul_f32_e32 v105, v25, v105
	v_add_f32_dpp v82, v82, v82 row_half_mirror row_mask:0xf bank_mask:0xf bound_ctrl:1
	global_store_dwordx4 v[112:113], v[104:107], off offset:2048
	s_nop 0
	v_add_f32_dpp v82, v82, v82 row_mirror row_mask:0xf bank_mask:0xf bound_ctrl:1
	v_cvt_f32_f16_sdwa v107, v75 dst_sel:DWORD dst_unused:UNUSED_PAD src0_sel:WORD_1
	v_readlane_b32 s10, v82, 16
	v_readlane_b32 s11, v82, 48
	v_readlane_b32 s0, v82, 0
	v_readlane_b32 s1, v82, 32
	v_mov_b32_e32 v82, s10
	v_mov_b32_e32 v83, s11
	v_add_f32_e32 v82, s0, v82
	v_add_f32_e32 v83, s1, v83
	v_cvt_f32_f16_e32 v106, v75
	v_add_f32_e32 v82, v82, v83
	v_fmamk_f32 v82, v82, 0x3a000000, v151
	v_mul_f32_e32 v83, 0x4f800000, v82
	v_cmp_gt_f32_e32 vcc, s18, v82
	s_nop 1
	v_cndmask_b32_e32 v90, v82, v83, vcc
	v_sqrt_f32_e32 v91, v90
	v_mul_f32_e32 v82, v100, v98
	v_mul_f32_e32 v83, v101, v98
	v_add_u32_e32 v98, -1, v91
	v_fma_f32 v99, -v98, v91, v90
	v_cmp_ge_f32_e64 s[0:1], 0, v99
	v_add_u32_e32 v99, 1, v91
	s_nop 0
	v_cndmask_b32_e64 v98, v91, v98, s[0:1]
	v_fma_f32 v91, -v99, v91, v90
	v_cmp_lt_f32_e64 s[0:1], 0, v91
	s_nop 1
	v_cndmask_b32_e64 v91, v98, v99, s[0:1]
	v_mul_f32_e32 v98, 0x37800000, v91
	v_cndmask_b32_e32 v91, v91, v98, vcc
	v_cmp_class_f32_e32 vcc, v90, v152
	s_nop 1
	v_cndmask_b32_e32 v98, v91, v90, vcc
	v_div_scale_f32 v99, s[0:1], v98, v98, 1.0
	v_rcp_f32_e32 v100, v99
	v_mul_f32_e32 v90, v30, v88
	v_mul_f32_e32 v91, v31, v89
	v_mul_f32_e32 v88, v28, v82
	v_mul_f32_e32 v89, v29, v83
	global_store_dwordx4 v[112:113], v[88:91], off offset:3072
	v_fma_f32 v82, -v99, v100, 1.0
	v_fmac_f32_e32 v100, v82, v100
	v_div_scale_f32 v82, vcc, 1.0, v98, 1.0
	v_mul_f32_e32 v83, v82, v100
	v_fma_f32 v88, -v99, v83, v82
	v_fmac_f32_e32 v83, v88, v100
	v_fma_f32 v82, -v99, v83, v82
	v_div_fmas_f32 v82, v82, v100, v83
	v_div_fixup_f32 v82, v82, v98, 1.0
	s_lshl_b64 s[0:1], s[8:9], 2
	s_add_u32 s0, s24, s0
	v_mul_f32_e32 v88, v108, v82
	v_mul_f32_e32 v89, v109, v82
	v_mul_f32_e32 v90, v110, v82
	v_mul_f32_e32 v91, v111, v82
	s_addc_u32 s1, s25, s1
	v_mul_f32_e32 v90, v2, v90
	v_mul_f32_e32 v91, v3, v91
	v_mul_f32_e32 v88, v0, v88
	v_mul_f32_e32 v89, v1, v89
	global_store_dwordx4 v48, v[88:91], s[0:1]
	v_lshl_add_u64 v[98:99], s[0:1], 0, v[48:49]
	v_cvt_f32_f16_sdwa v109, v72 dst_sel:DWORD dst_unused:UNUSED_PAD src0_sel:WORD_1
	v_mul_f32_e32 v88, v96, v82
	v_mul_f32_e32 v89, v97, v82
	v_mul_f32_e32 v90, v114, v82
	v_mul_f32_e32 v91, v115, v82
	v_mul_f32_e32 v88, v4, v88
	v_mul_f32_e32 v89, v5, v89
	v_mul_f32_e32 v90, v6, v90
	v_mul_f32_e32 v91, v7, v91
	global_store_dwordx4 v48, v[88:91], s[0:1] offset:1024
	v_add_co_u32_e32 v96, vcc, s16, v98
	s_nop 0
	v_mul_f32_e32 v88, v116, v82
	v_mul_f32_e32 v89, v117, v82
	v_mul_f32_e32 v90, v118, v82
	v_mul_f32_e32 v91, v119, v82
	v_mul_f32_e32 v88, v8, v88
	v_mul_f32_e32 v89, v9, v89
	v_mul_f32_e32 v90, v10, v90
	v_mul_f32_e32 v91, v11, v91
	global_store_dwordx4 v48, v[88:91], s[0:1] offset:2048
	v_addc_co_u32_e32 v97, vcc, 0, v99, vcc
	s_nop 0
	v_mul_f32_e32 v88, v120, v82
	v_mul_f32_e32 v89, v121, v82
	v_mul_f32_e32 v90, v122, v82
	v_mul_f32_e32 v91, v123, v82
	v_mul_f32_e32 v88, v12, v88
	v_mul_f32_e32 v89, v13, v89
	v_mul_f32_e32 v90, v14, v90
	v_mul_f32_e32 v91, v15, v91
	global_store_dwordx4 v48, v[88:91], s[0:1] offset:3072
	v_cvt_f32_f16_sdwa v99, v79 dst_sel:DWORD dst_unused:UNUSED_PAD src0_sel:WORD_1
	v_cvt_f32_f16_e32 v98, v79
	v_mul_f32_e32 v88, v124, v82
	v_mul_f32_e32 v89, v125, v82
	v_mul_f32_e32 v90, v126, v82
	v_mul_f32_e32 v91, v127, v82
	v_mul_f32_e32 v88, v16, v88
; #define GAS __attribute__((address_space(1)))
; #define LAS __attribute__((address_space(3)))
; #define FN_LOAD(dst, k_) do { const GAS v2u* xr_ = (const GAS v2u*)(X + (size_t)(nw + 2048 * (k_)) * D) + F.lane; \
;         _Pragma("unroll") for (int j = 0; j < 8; ++j) dst[j] = __builtin_nontemporal_load(xr_ + 64 * j); } while (0)
; __device__ __forceinline__ void final_norm_phase2(const Args& a, Frame& F) {
;     ...
;     FN_LOAD(r0, 0); FN_LOAD(r1, 1); FN_LOAD(r2, 2); FN_LOAD(r3, 3); FN_LOAD(r4, 4); FN_LOAD(r5, 5); FN_LOAD(r6, 6); FN_LOAD(r7, 7);
;     for (int q = F.tid; q < D / 4; q += NWAVES * 64) ((LAS f32x4*)GL)[q] = ((const GAS f32x4*)gain)[q];
;     asm volatile("s_waitcnt lgkmcnt(0)" ::: "memory"); __builtin_amdgcn_s_barrier(); asm volatile("" ::: "memory");
;     FN_FINISH(r0, 0); FN_FINISH(r1, 1); FN_FINISH(r2, 2); FN_FINISH(r3, 3); FN_FINISH(r4, 4); FN_FINISH(r5, 5); FN_FINISH(r6, 6); FN_FINISH(r7, 7);
	v_mul_f32_e32 v89, v17, v89
	v_mul_f32_e32 v90, v18, v90
	v_mul_f32_e32 v91, v19, v91
	global_store_dwordx4 v[96:97], v[88:91], off
	v_mov_b32_e32 v103, v99
	v_cvt_f32_f16_e32 v108, v72
	v_mul_f32_e32 v88, v92, v82
	v_mul_f32_e32 v89, v93, v82
	v_mul_f32_e32 v90, v94, v82
	v_mul_f32_e32 v91, v95, v82
	v_cvt_f32_f16_sdwa v93, v80 dst_sel:DWORD dst_unused:UNUSED_PAD src0_sel:WORD_1
	v_cvt_f32_f16_sdwa v95, v81 dst_sel:DWORD dst_unused:UNUSED_PAD src0_sel:WORD_1
	v_cvt_f32_f16_e32 v94, v81
	v_cvt_f32_f16_sdwa v81, v78 dst_sel:DWORD dst_unused:UNUSED_PAD src0_sel:WORD_1
	v_cvt_f32_f16_e32 v92, v80
	v_cvt_f32_f16_e32 v80, v78
	v_mov_b32_e32 v100, v93
	v_mov_b32_e32 v101, v81
	v_mov_b32_e32 v78, v92
	v_mov_b32_e32 v79, v80
	v_mul_f32_e32 v100, v100, v100
	v_mul_f32_e32 v101, v101, v101
	v_mov_b32_e32 v102, v95
	v_fma_f32 v78, v78, v78, v100
	v_fma_f32 v79, v79, v79, v101
	v_mov_b32_e32 v100, v94
	v_mov_b32_e32 v101, v98
	v_mul_f32_e32 v102, v102, v102
	v_mul_f32_e32 v103, v103, v103
	v_cvt_f32_f16_sdwa v111, v73 dst_sel:DWORD dst_unused:UNUSED_PAD src0_sel:WORD_1
	v_fma_f32 v100, v100, v100, v102
	v_fma_f32 v101, v101, v101, v103
	v_cvt_f32_f16_sdwa v103, v77 dst_sel:DWORD dst_unused:UNUSED_PAD src0_sel:WORD_1
	v_add_f32_e32 v78, v78, v100
	v_add_f32_e32 v79, v79, v101
	v_cvt_f32_f16_sdwa v101, v76 dst_sel:DWORD dst_unused:UNUSED_PAD src0_sel:WORD_1
	v_cvt_f32_f16_e32 v100, v76
	v_cvt_f32_f16_e32 v102, v77
	v_mov_b32_e32 v105, v103
	v_mov_b32_e32 v104, v101
	v_mov_b32_e32 v76, v100
	v_mov_b32_e32 v77, v102
	v_mul_f32_e32 v104, v104, v104
	v_mul_f32_e32 v105, v105, v105
	v_cvt_f32_f16_e32 v110, v73
	v_fma_f32 v76, v76, v76, v104
	v_fma_f32 v77, v77, v77, v105
	v_cvt_f32_f16_sdwa v105, v74 dst_sel:DWORD dst_unused:UNUSED_PAD src0_sel:WORD_1
	v_cvt_f32_f16_e32 v104, v74
	v_mul_f32_e32 v72, v107, v107
	v_pk_add_f32 v[78:79], v[78:79], v[78:79] op_sel:[0,1] op_sel_hi:[1,0]
	v_mul_f32_e32 v74, v105, v105
	v_pk_add_f32 v[76:77], v[76:77], v[76:77] op_sel:[0,1] op_sel_hi:[1,0]
	v_fma_f32 v75, v105, v105, v74
	v_fma_f32 v74, v104, v104, v74
	v_fma_f32 v73, v107, v107, v72
	v_fma_f32 v72, v106, v106, v72
	v_mul_f32_e32 v112, v108, v108
	v_mul_f32_e32 v113, v109, v109
	v_mul_f32_e32 v114, v110, v110
	v_mul_f32_e32 v115, v111, v111
	v_mov_b32_e32 v79, v112
	v_mov_b32_e32 v77, v113
	v_mov_b32_e32 v75, v114
	v_mov_b32_e32 v73, v115
	v_add_f32_e32 v76, v78, v76
	v_add_f32_e32 v77, v79, v77
	v_add_f32_e32 v72, v74, v72
	v_add_f32_e32 v73, v75, v73
	v_cvt_f32_f16_sdwa v79, v71 dst_sel:DWORD dst_unused:UNUSED_PAD src0_sel:WORD_1
	v_add_f32_e32 v72, v76, v72
	v_add_f32_e32 v73, v77, v73
	v_cvt_f32_f16_sdwa v77, v70 dst_sel:DWORD dst_unused:UNUSED_PAD src0_sel:WORD_1
	v_cvt_f32_f16_e32 v76, v70
	v_cvt_f32_f16_e32 v78, v71
	v_cvt_f32_f16_sdwa v113, v68 dst_sel:DWORD dst_unused:UNUSED_PAD src0_sel:WORD_1
	v_cvt_f32_f16_e32 v112, v68
	v_mov_b32_e32 v74, v77
	v_mov_b32_e32 v75, v79
	v_mov_b32_e32 v70, v76
	v_mov_b32_e32 v71, v78
	v_mul_f32_e32 v74, v74, v74
	v_mul_f32_e32 v75, v75, v75
	v_cvt_f32_f16_sdwa v115, v69 dst_sel:DWORD dst_unused:UNUSED_PAD src0_sel:WORD_1
	v_fma_f32 v70, v70, v70, v74
	v_fma_f32 v71, v71, v71, v75
	v_mul_f32_e32 v68, v113, v113
	v_add_f32_e32 v74, v70, v71
	v_add_f32_e32 v75, v71, v70
	v_cvt_f32_f16_e32 v114, v69
	v_fma_f32 v116, v112, v112, v68
	v_fma_f32 v117, v113, v113, v68
	v_cvt_f32_f16_sdwa v69, v66 dst_sel:DWORD dst_unused:UNUSED_PAD src0_sel:WORD_1
	v_cvt_f32_f16_e32 v68, v66
	v_cvt_f32_f16_sdwa v71, v67 dst_sel:DWORD dst_unused:UNUSED_PAD src0_sel:WORD_1
	v_cvt_f32_f16_e32 v70, v67
	v_mul_f32_e32 v66, v115, v115
	v_pk_add_f32 v[72:73], v[72:73], v[72:73] op_sel:[0,1] op_sel_hi:[1,0]
	v_fma_f32 v67, v115, v115, v66
	v_fma_f32 v66, v114, v114, v66
	v_mul_f32_e32 v118, v68, v68
	v_mul_f32_e32 v119, v69, v69
	v_mul_f32_e32 v120, v70, v70
	v_mul_f32_e32 v121, v71, v71
	v_mov_b32_e32 v73, v118
	v_mov_b32_e32 v75, v119
	v_mov_b32_e32 v117, v120
	v_mov_b32_e32 v67, v121
	v_add_f32_e32 v72, v72, v74
	v_add_f32_e32 v73, v73, v75
	v_add_f32_e32 v66, v116, v66
	v_add_f32_e32 v67, v117, v67
	v_mul_f32_e32 v90, v22, v90
	v_mul_f32_e32 v91, v23, v91
	v_add_f32_e32 v66, v72, v66
	v_add_f32_e32 v67, v73, v67
	v_mul_f32_e32 v88, v20, v88
	v_mul_f32_e32 v89, v21, v89
	v_add_f32_e32 v66, v66, v67
	global_store_dwordx4 v[96:97], v[88:91], off offset:1024
	v_mul_f32_e32 v72, v86, v82
	v_mul_f32_e32 v73, v87, v82
	v_add_f32_dpp v66, v66, v66 quad_perm:[1,0,3,2] row_mask:0xf bank_mask:0xf bound_ctrl:1
	v_mul_f32_e32 v88, v128, v82
	v_mul_f32_e32 v89, v129, v82
	v_mul_f32_e32 v90, v130, v82
	v_mul_f32_e32 v91, v131, v82
	v_add_f32_dpp v66, v66, v66 quad_perm:[2,3,0,1] row_mask:0xf bank_mask:0xf bound_ctrl:1
	v_mul_f32_e32 v90, v26, v90
	v_mul_f32_e32 v91, v27, v91
	v_mul_f32_e32 v88, v24, v88
	v_mul_f32_e32 v89, v25, v89
	v_add_f32_dpp v66, v66, v66 row_half_mirror row_mask:0xf bank_mask:0xf bound_ctrl:1
	global_store_dwordx4 v[96:97], v[88:91], off offset:2048
	s_nop 0
	v_add_f32_dpp v66, v66, v66 row_mirror row_mask:0xf bank_mask:0xf bound_ctrl:1
	v_cvt_f32_f16_sdwa v91, v59 dst_sel:DWORD dst_unused:UNUSED_PAD src0_sel:WORD_1
	v_readlane_b32 s8, v66, 16
	v_readlane_b32 s9, v66, 48
	v_readlane_b32 s0, v66, 0
	v_readlane_b32 s1, v66, 32
	v_mov_b32_e32 v66, s8
	v_mov_b32_e32 v67, s9
	v_add_f32_e32 v66, s0, v66
	v_add_f32_e32 v67, s1, v67
	v_cvt_f32_f16_e32 v90, v59
	v_add_f32_e32 v66, v66, v67
	v_fmamk_f32 v66, v66, 0x3a000000, v151
	v_mul_f32_e32 v67, 0x4f800000, v66
	v_cmp_gt_f32_e32 vcc, s18, v66
	s_nop 1
	v_cndmask_b32_e32 v74, v66, v67, vcc
	v_sqrt_f32_e32 v75, v74
	v_mul_f32_e32 v66, v84, v82
	v_mul_f32_e32 v67, v85, v82
	v_add_u32_e32 v82, -1, v75
; #define GAS __attribute__((address_space(1)))
; #define LAS __attribute__((address_space(3)))
; #define FN_LOAD(dst, k_) do { const GAS v2u* xr_ = (const GAS v2u*)(X + (size_t)(nw + 2048 * (k_)) * D) + F.lane; \
;         _Pragma("unroll") for (int j = 0; j < 8; ++j) dst[j] = __builtin_nontemporal_load(xr_ + 64 * j); } while (0)
; __device__ __forceinline__ void final_norm_phase2(const Args& a, Frame& F) {
;     ...
;     FN_LOAD(r0, 0); FN_LOAD(r1, 1); FN_LOAD(r2, 2); FN_LOAD(r3, 3); FN_LOAD(r4, 4); FN_LOAD(r5, 5); FN_LOAD(r6, 6); FN_LOAD(r7, 7);
;     for (int q = F.tid; q < D / 4; q += NWAVES * 64) ((LAS f32x4*)GL)[q] = ((const GAS f32x4*)gain)[q];
;     asm volatile("s_waitcnt lgkmcnt(0)" ::: "memory"); __builtin_amdgcn_s_barrier(); asm volatile("" ::: "memory");
;     FN_FINISH(r0, 0); FN_FINISH(r1, 1); FN_FINISH(r2, 2); FN_FINISH(r3, 3); FN_FINISH(r4, 4); FN_FINISH(r5, 5); FN_FINISH(r6, 6); FN_FINISH(r7, 7);
	v_fma_f32 v83, -v82, v75, v74
	v_cmp_ge_f32_e64 s[0:1], 0, v83
	v_add_u32_e32 v83, 1, v75
	s_nop 0
	v_cndmask_b32_e64 v82, v75, v82, s[0:1]
	v_fma_f32 v75, -v83, v75, v74
	v_cmp_lt_f32_e64 s[0:1], 0, v75
	s_nop 1
	v_cndmask_b32_e64 v75, v82, v83, s[0:1]
	v_mul_f32_e32 v82, 0x37800000, v75
	v_cndmask_b32_e32 v75, v75, v82, vcc
	v_cmp_class_f32_e32 vcc, v74, v152
	s_nop 1
	v_cndmask_b32_e32 v82, v75, v74, vcc
	v_div_scale_f32 v83, s[0:1], v82, v82, 1.0
	v_rcp_f32_e32 v84, v83
	v_mul_f32_e32 v74, v30, v72
	v_mul_f32_e32 v75, v31, v73
	v_mul_f32_e32 v72, v28, v66
	v_mul_f32_e32 v73, v29, v67
	global_store_dwordx4 v[96:97], v[72:75], off offset:3072
	v_fma_f32 v66, -v83, v84, 1.0
	v_fmac_f32_e32 v84, v66, v84
	v_div_scale_f32 v66, vcc, 1.0, v82, 1.0
	v_mul_f32_e32 v67, v66, v84
	v_fma_f32 v72, -v83, v67, v66
	v_fmac_f32_e32 v67, v72, v84
	v_fma_f32 v66, -v83, v67, v66
	v_div_fmas_f32 v66, v66, v84, v67
	v_div_fixup_f32 v66, v66, v82, 1.0
	s_lshl_b64 s[0:1], s[6:7], 2
	s_add_u32 s0, s24, s0
	v_mul_f32_e32 v72, v92, v66
	v_mul_f32_e32 v73, v93, v66
	v_mul_f32_e32 v74, v94, v66
	v_mul_f32_e32 v75, v95, v66
	s_addc_u32 s1, s25, s1
	v_mul_f32_e32 v74, v2, v74
	v_mul_f32_e32 v75, v3, v75
	v_mul_f32_e32 v72, v0, v72
	v_mul_f32_e32 v73, v1, v73
	global_store_dwordx4 v48, v[72:75], s[0:1]
	v_lshl_add_u64 v[82:83], s[0:1], 0, v[48:49]
	v_cvt_f32_f16_sdwa v93, v56 dst_sel:DWORD dst_unused:UNUSED_PAD src0_sel:WORD_1
	v_mul_f32_e32 v72, v80, v66
	v_mul_f32_e32 v73, v81, v66
	v_mul_f32_e32 v74, v98, v66
	v_mul_f32_e32 v75, v99, v66
	v_mul_f32_e32 v72, v4, v72
	v_mul_f32_e32 v73, v5, v73
	v_mul_f32_e32 v74, v6, v74
	v_mul_f32_e32 v75, v7, v75
	global_store_dwordx4 v48, v[72:75], s[0:1] offset:1024
	v_add_co_u32_e32 v80, vcc, s16, v82
	s_nop 0
	v_mul_f32_e32 v72, v100, v66
	v_mul_f32_e32 v73, v101, v66
	v_mul_f32_e32 v74, v102, v66
	v_mul_f32_e32 v75, v103, v66
	v_mul_f32_e32 v72, v8, v72
	v_mul_f32_e32 v73, v9, v73
	v_mul_f32_e32 v74, v10, v74
	v_mul_f32_e32 v75, v11, v75
	global_store_dwordx4 v48, v[72:75], s[0:1] offset:2048
	v_addc_co_u32_e32 v81, vcc, 0, v83, vcc
	s_nop 0
	v_mul_f32_e32 v72, v104, v66
	v_mul_f32_e32 v73, v105, v66
	v_mul_f32_e32 v74, v106, v66
	v_mul_f32_e32 v75, v107, v66
	v_mul_f32_e32 v72, v12, v72
	v_mul_f32_e32 v73, v13, v73
	v_mul_f32_e32 v74, v14, v74
	v_mul_f32_e32 v75, v15, v75
	global_store_dwordx4 v48, v[72:75], s[0:1] offset:3072
	v_cvt_f32_f16_sdwa v83, v63 dst_sel:DWORD dst_unused:UNUSED_PAD src0_sel:WORD_1
	v_cvt_f32_f16_e32 v82, v63
	v_mul_f32_e32 v72, v108, v66
	v_mul_f32_e32 v73, v109, v66
	v_mul_f32_e32 v74, v110, v66
	v_mul_f32_e32 v75, v111, v66
	v_mul_f32_e32 v72, v16, v72
	v_mul_f32_e32 v73, v17, v73
	v_mul_f32_e32 v74, v18, v74
	v_mul_f32_e32 v75, v19, v75
	global_store_dwordx4 v[80:81], v[72:75], off
	v_mov_b32_e32 v87, v83
	v_cvt_f32_f16_e32 v92, v56
	v_mul_f32_e32 v72, v76, v66
	v_mul_f32_e32 v73, v77, v66
	v_mul_f32_e32 v74, v78, v66
	v_mul_f32_e32 v75, v79, v66
	v_cvt_f32_f16_sdwa v77, v64 dst_sel:DWORD dst_unused:UNUSED_PAD src0_sel:WORD_1
	v_cvt_f32_f16_sdwa v79, v65 dst_sel:DWORD dst_unused:UNUSED_PAD src0_sel:WORD_1
	v_cvt_f32_f16_e32 v78, v65
	v_cvt_f32_f16_sdwa v65, v62 dst_sel:DWORD dst_unused:UNUSED_PAD src0_sel:WORD_1
	v_cvt_f32_f16_e32 v76, v64
	v_cvt_f32_f16_e32 v64, v62
	v_mov_b32_e32 v84, v77
	v_mov_b32_e32 v85, v65
	v_mov_b32_e32 v62, v76
	v_mov_b32_e32 v63, v64
	v_mul_f32_e32 v84, v84, v84
	v_mul_f32_e32 v85, v85, v85
	v_mov_b32_e32 v86, v79
	v_fma_f32 v62, v62, v62, v84
	v_fma_f32 v63, v63, v63, v85
	v_mov_b32_e32 v84, v78
	v_mov_b32_e32 v85, v82
	v_mul_f32_e32 v86, v86, v86
	v_mul_f32_e32 v87, v87, v87
	v_cvt_f32_f16_sdwa v95, v57 dst_sel:DWORD dst_unused:UNUSED_PAD src0_sel:WORD_1
	v_fma_f32 v84, v84, v84, v86
	v_fma_f32 v85, v85, v85, v87
	v_cvt_f32_f16_sdwa v87, v61 dst_sel:DWORD dst_unused:UNUSED_PAD src0_sel:WORD_1
	v_add_f32_e32 v62, v62, v84
	v_add_f32_e32 v63, v63, v85
	v_cvt_f32_f16_sdwa v85, v60 dst_sel:DWORD dst_unused:UNUSED_PAD src0_sel:WORD_1
	v_cvt_f32_f16_e32 v84, v60
	v_cvt_f32_f16_e32 v86, v61
	v_mov_b32_e32 v89, v87
	v_mov_b32_e32 v88, v85
	v_mov_b32_e32 v60, v84
	v_mov_b32_e32 v61, v86
	v_mul_f32_e32 v88, v88, v88
	v_mul_f32_e32 v89, v89, v89
	v_cvt_f32_f16_e32 v94, v57
	v_fma_f32 v60, v60, v60, v88
	v_fma_f32 v61, v61, v61, v89
	v_cvt_f32_f16_sdwa v89, v58 dst_sel:DWORD dst_unused:UNUSED_PAD src0_sel:WORD_1
	v_cvt_f32_f16_e32 v88, v58
	v_mul_f32_e32 v56, v91, v91
	v_pk_add_f32 v[62:63], v[62:63], v[62:63] op_sel:[0,1] op_sel_hi:[1,0]
	v_mul_f32_e32 v58, v89, v89
	v_pk_add_f32 v[60:61], v[60:61], v[60:61] op_sel:[0,1] op_sel_hi:[1,0]
	v_fma_f32 v59, v89, v89, v58
	v_fma_f32 v58, v88, v88, v58
	v_fma_f32 v57, v91, v91, v56
	v_fma_f32 v56, v90, v90, v56
	v_mul_f32_e32 v96, v92, v92
	v_mul_f32_e32 v97, v93, v93
	v_mul_f32_e32 v98, v94, v94
	v_mul_f32_e32 v99, v95, v95
	v_mov_b32_e32 v63, v96
	v_mov_b32_e32 v61, v97
	v_mov_b32_e32 v59, v98
	v_mov_b32_e32 v57, v99
	v_add_f32_e32 v60, v62, v60
	v_add_f32_e32 v61, v63, v61
	v_add_f32_e32 v56, v58, v56
	v_add_f32_e32 v57, v59, v57
	v_cvt_f32_f16_sdwa v63, v55 dst_sel:DWORD dst_unused:UNUSED_PAD src0_sel:WORD_1
	v_add_f32_e32 v56, v60, v56
	v_add_f32_e32 v57, v61, v57
	v_cvt_f32_f16_sdwa v61, v54 dst_sel:DWORD dst_unused:UNUSED_PAD src0_sel:WORD_1
	v_cvt_f32_f16_e32 v60, v54
	v_cvt_f32_f16_e32 v62, v55
	v_cvt_f32_f16_sdwa v97, v52 dst_sel:DWORD dst_unused:UNUSED_PAD src0_sel:WORD_1
	v_cvt_f32_f16_e32 v96, v52
	v_mov_b32_e32 v58, v61
	v_mov_b32_e32 v59, v63
	v_mov_b32_e32 v54, v60
	v_mov_b32_e32 v55, v62
	v_mul_f32_e32 v58, v58, v58
	v_mul_f32_e32 v59, v59, v59
	v_cvt_f32_f16_sdwa v99, v53 dst_sel:DWORD dst_unused:UNUSED_PAD src0_sel:WORD_1
; #define GAS __attribute__((address_space(1)))
; #define LAS __attribute__((address_space(3)))
; #define FN_LOAD(dst, k_) do { const GAS v2u* xr_ = (const GAS v2u*)(X + (size_t)(nw + 2048 * (k_)) * D) + F.lane; \
;         _Pragma("unroll") for (int j = 0; j < 8; ++j) dst[j] = __builtin_nontemporal_load(xr_ + 64 * j); } while (0)
; __device__ __forceinline__ void final_norm_phase2(const Args& a, Frame& F) {
;     ...
;     FN_LOAD(r0, 0); FN_LOAD(r1, 1); FN_LOAD(r2, 2); FN_LOAD(r3, 3); FN_LOAD(r4, 4); FN_LOAD(r5, 5); FN_LOAD(r6, 6); FN_LOAD(r7, 7);
;     for (int q = F.tid; q < D / 4; q += NWAVES * 64) ((LAS f32x4*)GL)[q] = ((const GAS f32x4*)gain)[q];
;     asm volatile("s_waitcnt lgkmcnt(0)" ::: "memory"); __builtin_amdgcn_s_barrier(); asm volatile("" ::: "memory");
;     FN_FINISH(r0, 0); FN_FINISH(r1, 1); FN_FINISH(r2, 2); FN_FINISH(r3, 3); FN_FINISH(r4, 4); FN_FINISH(r5, 5); FN_FINISH(r6, 6); FN_FINISH(r7, 7);
	v_fma_f32 v54, v54, v54, v58
	v_fma_f32 v55, v55, v55, v59
	v_mul_f32_e32 v52, v97, v97
	v_add_f32_e32 v58, v54, v55
	v_add_f32_e32 v59, v55, v54
	v_cvt_f32_f16_e32 v98, v53
	v_fma_f32 v100, v96, v96, v52
	v_fma_f32 v101, v97, v97, v52
	v_cvt_f32_f16_sdwa v53, v50 dst_sel:DWORD dst_unused:UNUSED_PAD src0_sel:WORD_1
	v_cvt_f32_f16_e32 v52, v50
	v_cvt_f32_f16_sdwa v55, v51 dst_sel:DWORD dst_unused:UNUSED_PAD src0_sel:WORD_1
	v_cvt_f32_f16_e32 v54, v51
	v_mul_f32_e32 v50, v99, v99
	v_pk_add_f32 v[56:57], v[56:57], v[56:57] op_sel:[0,1] op_sel_hi:[1,0]
	v_fma_f32 v51, v99, v99, v50
	v_fma_f32 v50, v98, v98, v50
	v_mul_f32_e32 v102, v52, v52
	v_mul_f32_e32 v103, v53, v53
	v_mul_f32_e32 v104, v54, v54
	v_mul_f32_e32 v105, v55, v55
	v_mov_b32_e32 v57, v102
	v_mov_b32_e32 v59, v103
	v_mov_b32_e32 v101, v104
	v_mov_b32_e32 v51, v105
	v_add_f32_e32 v56, v56, v58
	v_add_f32_e32 v57, v57, v59
	v_add_f32_e32 v50, v100, v50
	v_add_f32_e32 v51, v101, v51
	v_mul_f32_e32 v74, v22, v74
	v_mul_f32_e32 v75, v23, v75
	v_add_f32_e32 v50, v56, v50
	v_add_f32_e32 v51, v57, v51
	v_mul_f32_e32 v72, v20, v72
	v_mul_f32_e32 v73, v21, v73
	v_add_f32_e32 v50, v50, v51
	global_store_dwordx4 v[80:81], v[72:75], off offset:1024
	v_mul_f32_e32 v56, v70, v66
	v_mul_f32_e32 v57, v71, v66
	v_add_f32_dpp v50, v50, v50 quad_perm:[1,0,3,2] row_mask:0xf bank_mask:0xf bound_ctrl:1
	v_mul_f32_e32 v72, v112, v66
	v_mul_f32_e32 v73, v113, v66
	v_mul_f32_e32 v74, v114, v66
	v_mul_f32_e32 v75, v115, v66
	v_add_f32_dpp v50, v50, v50 quad_perm:[2,3,0,1] row_mask:0xf bank_mask:0xf bound_ctrl:1
	v_mul_f32_e32 v74, v26, v74
	v_mul_f32_e32 v75, v27, v75
	v_mul_f32_e32 v72, v24, v72
	v_mul_f32_e32 v73, v25, v73
	v_add_f32_dpp v50, v50, v50 row_half_mirror row_mask:0xf bank_mask:0xf bound_ctrl:1
	global_store_dwordx4 v[80:81], v[72:75], off offset:2048
	s_nop 0
	v_add_f32_dpp v50, v50, v50 row_mirror row_mask:0xf bank_mask:0xf bound_ctrl:1
	v_cvt_f32_f16_sdwa v75, v41 dst_sel:DWORD dst_unused:UNUSED_PAD src0_sel:WORD_1
	v_readlane_b32 s6, v50, 16
	v_readlane_b32 s7, v50, 48
	v_readlane_b32 s0, v50, 0
	v_readlane_b32 s1, v50, 32
	v_mov_b32_e32 v50, s6
	v_mov_b32_e32 v51, s7
	v_add_f32_e32 v50, s0, v50
	v_add_f32_e32 v51, s1, v51
	v_cvt_f32_f16_e32 v74, v41
	v_add_f32_e32 v50, v50, v51
	v_fmamk_f32 v50, v50, 0x3a000000, v151
	v_mul_f32_e32 v51, 0x4f800000, v50
	v_cmp_gt_f32_e32 vcc, s18, v50
	s_nop 1
	v_cndmask_b32_e32 v58, v50, v51, vcc
	v_sqrt_f32_e32 v59, v58
	v_mul_f32_e32 v50, v68, v66
	v_mul_f32_e32 v51, v69, v66
	v_add_u32_e32 v66, -1, v59
	v_fma_f32 v67, -v66, v59, v58
	v_cmp_ge_f32_e64 s[0:1], 0, v67
	v_add_u32_e32 v67, 1, v59
	s_nop 0
	v_cndmask_b32_e64 v66, v59, v66, s[0:1]
	v_fma_f32 v59, -v67, v59, v58
	v_cmp_lt_f32_e64 s[0:1], 0, v59
	s_nop 1
	v_cndmask_b32_e64 v59, v66, v67, s[0:1]
	v_mul_f32_e32 v66, 0x37800000, v59
	v_cndmask_b32_e32 v59, v59, v66, vcc
	v_cmp_class_f32_e32 vcc, v58, v152
	s_nop 1
	v_cndmask_b32_e32 v66, v59, v58, vcc
	v_div_scale_f32 v67, s[0:1], v66, v66, 1.0
	v_rcp_f32_e32 v68, v67
	v_mul_f32_e32 v58, v30, v56
	v_mul_f32_e32 v59, v31, v57
	v_mul_f32_e32 v56, v28, v50
	v_mul_f32_e32 v57, v29, v51
	global_store_dwordx4 v[80:81], v[56:59], off offset:3072
	v_fma_f32 v50, -v67, v68, 1.0
	v_fmac_f32_e32 v68, v50, v68
	v_div_scale_f32 v50, vcc, 1.0, v66, 1.0
	v_mul_f32_e32 v51, v50, v68
	v_fma_f32 v56, -v67, v51, v50
	v_fmac_f32_e32 v51, v56, v68
	v_fma_f32 v50, -v67, v51, v50
	v_div_fmas_f32 v50, v50, v68, v51
	v_div_fixup_f32 v50, v50, v66, 1.0
	s_lshl_b64 s[0:1], s[4:5], 2
	s_add_u32 s0, s24, s0
	v_mul_f32_e32 v56, v76, v50
	v_mul_f32_e32 v57, v77, v50
	v_mul_f32_e32 v58, v78, v50
	v_mul_f32_e32 v59, v79, v50
	s_addc_u32 s1, s25, s1
	v_mul_f32_e32 v58, v2, v58
	v_mul_f32_e32 v59, v3, v59
	v_mul_f32_e32 v56, v0, v56
	v_mul_f32_e32 v57, v1, v57
	global_store_dwordx4 v48, v[56:59], s[0:1]
	v_lshl_add_u64 v[66:67], s[0:1], 0, v[48:49]
	v_cvt_f32_f16_sdwa v77, v38 dst_sel:DWORD dst_unused:UNUSED_PAD src0_sel:WORD_1
	v_mul_f32_e32 v56, v64, v50
	v_mul_f32_e32 v57, v65, v50
	v_mul_f32_e32 v58, v82, v50
	v_mul_f32_e32 v59, v83, v50
	v_mul_f32_e32 v56, v4, v56
	v_mul_f32_e32 v57, v5, v57
	v_mul_f32_e32 v58, v6, v58
	v_mul_f32_e32 v59, v7, v59
	global_store_dwordx4 v48, v[56:59], s[0:1] offset:1024
	v_add_co_u32_e32 v64, vcc, s16, v66
	s_nop 0
	v_mul_f32_e32 v56, v84, v50
	v_mul_f32_e32 v57, v85, v50
	v_mul_f32_e32 v58, v86, v50
	v_mul_f32_e32 v59, v87, v50
	v_mul_f32_e32 v56, v8, v56
	v_mul_f32_e32 v57, v9, v57
	v_mul_f32_e32 v58, v10, v58
	v_mul_f32_e32 v59, v11, v59
	global_store_dwordx4 v48, v[56:59], s[0:1] offset:2048
	v_addc_co_u32_e32 v65, vcc, 0, v67, vcc
	s_nop 0
	v_mul_f32_e32 v56, v88, v50
	v_mul_f32_e32 v57, v89, v50
	v_mul_f32_e32 v58, v90, v50
	v_mul_f32_e32 v59, v91, v50
	v_mul_f32_e32 v56, v12, v56
	v_mul_f32_e32 v57, v13, v57
	v_mul_f32_e32 v58, v14, v58
	v_mul_f32_e32 v59, v15, v59
	global_store_dwordx4 v48, v[56:59], s[0:1] offset:3072
	v_cvt_f32_f16_sdwa v67, v45 dst_sel:DWORD dst_unused:UNUSED_PAD src0_sel:WORD_1
	v_cvt_f32_f16_e32 v66, v45
	v_mul_f32_e32 v56, v92, v50
	v_mul_f32_e32 v57, v93, v50
	v_mul_f32_e32 v58, v94, v50
	v_mul_f32_e32 v59, v95, v50
	v_mul_f32_e32 v56, v16, v56
	v_mul_f32_e32 v57, v17, v57
	v_mul_f32_e32 v58, v18, v58
	v_mul_f32_e32 v59, v19, v59
	global_store_dwordx4 v[64:65], v[56:59], off
	v_mov_b32_e32 v71, v67
	v_cvt_f32_f16_e32 v76, v38
	v_mul_f32_e32 v56, v60, v50
	v_mul_f32_e32 v57, v61, v50
	v_mul_f32_e32 v58, v62, v50
	v_mul_f32_e32 v59, v63, v50
	v_cvt_f32_f16_sdwa v61, v46 dst_sel:DWORD dst_unused:UNUSED_PAD src0_sel:WORD_1
	v_cvt_f32_f16_sdwa v63, v47 dst_sel:DWORD dst_unused:UNUSED_PAD src0_sel:WORD_1
; #define GAS __attribute__((address_space(1)))
; #define LAS __attribute__((address_space(3)))
; #define FN_LOAD(dst, k_) do { const GAS v2u* xr_ = (const GAS v2u*)(X + (size_t)(nw + 2048 * (k_)) * D) + F.lane; \
;         _Pragma("unroll") for (int j = 0; j < 8; ++j) dst[j] = __builtin_nontemporal_load(xr_ + 64 * j); } while (0)
; __device__ __forceinline__ void final_norm_phase2(const Args& a, Frame& F) {
;     ...
;     FN_LOAD(r0, 0); FN_LOAD(r1, 1); FN_LOAD(r2, 2); FN_LOAD(r3, 3); FN_LOAD(r4, 4); FN_LOAD(r5, 5); FN_LOAD(r6, 6); FN_LOAD(r7, 7);
;     for (int q = F.tid; q < D / 4; q += NWAVES * 64) ((LAS f32x4*)GL)[q] = ((const GAS f32x4*)gain)[q];
;     asm volatile("s_waitcnt lgkmcnt(0)" ::: "memory"); __builtin_amdgcn_s_barrier(); asm volatile("" ::: "memory");
;     FN_FINISH(r0, 0); FN_FINISH(r1, 1); FN_FINISH(r2, 2); FN_FINISH(r3, 3); FN_FINISH(r4, 4); FN_FINISH(r5, 5); FN_FINISH(r6, 6); FN_FINISH(r7, 7);
	v_cvt_f32_f16_e32 v62, v47
	v_cvt_f32_f16_sdwa v47, v44 dst_sel:DWORD dst_unused:UNUSED_PAD src0_sel:WORD_1
	v_cvt_f32_f16_e32 v60, v46
	v_cvt_f32_f16_e32 v46, v44
	v_mov_b32_e32 v68, v61
	v_mov_b32_e32 v69, v47
	v_mov_b32_e32 v44, v60
	v_mov_b32_e32 v45, v46
	v_mul_f32_e32 v68, v68, v68
	v_mul_f32_e32 v69, v69, v69
	v_mov_b32_e32 v70, v63
	v_fma_f32 v44, v44, v44, v68
	v_fma_f32 v45, v45, v45, v69
	v_mov_b32_e32 v68, v62
	v_mov_b32_e32 v69, v66
	v_mul_f32_e32 v70, v70, v70
	v_mul_f32_e32 v71, v71, v71
	v_cvt_f32_f16_sdwa v79, v39 dst_sel:DWORD dst_unused:UNUSED_PAD src0_sel:WORD_1
	v_fma_f32 v68, v68, v68, v70
	v_fma_f32 v69, v69, v69, v71
	v_cvt_f32_f16_sdwa v71, v43 dst_sel:DWORD dst_unused:UNUSED_PAD src0_sel:WORD_1
	v_add_f32_e32 v44, v44, v68
	v_add_f32_e32 v45, v45, v69
	v_cvt_f32_f16_sdwa v69, v42 dst_sel:DWORD dst_unused:UNUSED_PAD src0_sel:WORD_1
	v_cvt_f32_f16_e32 v68, v42
	v_cvt_f32_f16_e32 v70, v43
	v_mov_b32_e32 v73, v71
	v_mov_b32_e32 v72, v69
	v_mov_b32_e32 v42, v68
	v_mov_b32_e32 v43, v70
	v_mul_f32_e32 v72, v72, v72
	v_mul_f32_e32 v73, v73, v73
	v_cvt_f32_f16_e32 v78, v39
	v_fma_f32 v42, v42, v42, v72
	v_fma_f32 v43, v43, v43, v73
	v_cvt_f32_f16_sdwa v73, v40 dst_sel:DWORD dst_unused:UNUSED_PAD src0_sel:WORD_1
	v_cvt_f32_f16_e32 v72, v40
	v_mul_f32_e32 v38, v75, v75
	v_pk_add_f32 v[44:45], v[44:45], v[44:45] op_sel:[0,1] op_sel_hi:[1,0]
	v_mul_f32_e32 v40, v73, v73
	v_pk_add_f32 v[42:43], v[42:43], v[42:43] op_sel:[0,1] op_sel_hi:[1,0]
	v_fma_f32 v41, v73, v73, v40
	v_fma_f32 v40, v72, v72, v40
	v_fma_f32 v39, v75, v75, v38
	v_fma_f32 v38, v74, v74, v38
	v_mul_f32_e32 v80, v76, v76
	v_mul_f32_e32 v81, v77, v77
	v_mul_f32_e32 v82, v78, v78
	v_mul_f32_e32 v83, v79, v79
	v_mov_b32_e32 v45, v80
	v_mov_b32_e32 v43, v81
	v_mov_b32_e32 v41, v82
	v_mov_b32_e32 v39, v83
	v_add_f32_e32 v42, v44, v42
	v_add_f32_e32 v43, v45, v43
	v_add_f32_e32 v38, v40, v38
	v_add_f32_e32 v39, v41, v39
	v_cvt_f32_f16_sdwa v41, v36 dst_sel:DWORD dst_unused:UNUSED_PAD src0_sel:WORD_1
	v_add_f32_e32 v38, v42, v38
	v_add_f32_e32 v39, v43, v39
	v_cvt_f32_f16_sdwa v43, v37 dst_sel:DWORD dst_unused:UNUSED_PAD src0_sel:WORD_1
	v_cvt_f32_f16_e32 v40, v36
	v_cvt_f32_f16_e32 v42, v37
	v_mov_b32_e32 v44, v41
	v_mov_b32_e32 v45, v43
	v_mov_b32_e32 v36, v40
	v_mov_b32_e32 v37, v42
	v_mul_f32_e32 v44, v44, v44
	v_mul_f32_e32 v45, v45, v45
	v_cvt_f32_f16_sdwa v81, v35 dst_sel:DWORD dst_unused:UNUSED_PAD src0_sel:WORD_1
	v_fma_f32 v36, v36, v36, v44
	v_fma_f32 v37, v37, v37, v45
	v_cvt_f32_f16_sdwa v45, v34 dst_sel:DWORD dst_unused:UNUSED_PAD src0_sel:WORD_1
	v_cvt_f32_f16_e32 v44, v34
	v_cvt_f32_f16_e32 v80, v35
	v_cvt_f32_f16_sdwa v83, v32 dst_sel:DWORD dst_unused:UNUSED_PAD src0_sel:WORD_1
	v_cvt_f32_f16_e32 v82, v32
	v_cvt_f32_f16_sdwa v85, v33 dst_sel:DWORD dst_unused:UNUSED_PAD src0_sel:WORD_1
	v_cvt_f32_f16_e32 v84, v33
	v_mul_f32_e32 v34, v45, v45
	v_mul_f32_e32 v32, v81, v81
	v_pk_add_f32 v[38:39], v[38:39], v[38:39] op_sel:[0,1] op_sel_hi:[1,0]
	v_pk_add_f32 v[36:37], v[36:37], v[36:37] op_sel:[0,1] op_sel_hi:[1,0]
	v_fma_f32 v35, v45, v45, v34
	v_fma_f32 v34, v44, v44, v34
	v_fma_f32 v33, v81, v81, v32
	v_fma_f32 v32, v80, v80, v32
	v_mul_f32_e32 v86, v82, v82
	v_mul_f32_e32 v87, v83, v83
	v_mul_f32_e32 v88, v84, v84
	v_mul_f32_e32 v89, v85, v85
	v_mov_b32_e32 v39, v86
	v_mov_b32_e32 v37, v87
	v_mov_b32_e32 v35, v88
	v_mov_b32_e32 v33, v89
	v_add_f32_e32 v36, v38, v36
	v_add_f32_e32 v37, v39, v37
	v_add_f32_e32 v32, v34, v32
	v_add_f32_e32 v33, v35, v33
	v_mul_f32_e32 v34, v54, v50
	v_mul_f32_e32 v35, v55, v50
	v_add_f32_e32 v32, v36, v32
	v_add_f32_e32 v33, v37, v33
	v_mul_f32_e32 v34, v30, v34
	v_mul_f32_e32 v35, v31, v35
	v_add_f32_e32 v32, v32, v33
	v_mul_f32_e32 v58, v22, v58
	v_mul_f32_e32 v59, v23, v59
	v_mul_f32_e32 v56, v20, v56
	v_mul_f32_e32 v57, v21, v57
	v_add_f32_dpp v32, v32, v32 quad_perm:[1,0,3,2] row_mask:0xf bank_mask:0xf bound_ctrl:1
	global_store_dwordx4 v[64:65], v[56:59], off offset:1024
	s_nop 0
	v_add_f32_dpp v32, v32, v32 quad_perm:[2,3,0,1] row_mask:0xf bank_mask:0xf bound_ctrl:1
	v_mul_f32_e32 v56, v96, v50
	v_mul_f32_e32 v57, v97, v50
	v_mul_f32_e32 v58, v98, v50
	v_mul_f32_e32 v59, v99, v50
; #define GAS __attribute__((address_space(1)))
; #define LAS __attribute__((address_space(3)))
; #define FN_LOAD(dst, k_) do { const GAS v2u* xr_ = (const GAS v2u*)(X + (size_t)(nw + 2048 * (k_)) * D) + F.lane; \
;         _Pragma("unroll") for (int j = 0; j < 8; ++j) dst[j] = __builtin_nontemporal_load(xr_ + 64 * j); } while (0)
; __device__ __forceinline__ void final_norm_phase2(const Args& a, Frame& F) {
;     ...
;     FN_LOAD(r0, 0); FN_LOAD(r1, 1); FN_LOAD(r2, 2); FN_LOAD(r3, 3); FN_LOAD(r4, 4); FN_LOAD(r5, 5); FN_LOAD(r6, 6); FN_LOAD(r7, 7);
;     for (int q = F.tid; q < D / 4; q += NWAVES * 64) ((LAS f32x4*)GL)[q] = ((const GAS f32x4*)gain)[q];
;     asm volatile("s_waitcnt lgkmcnt(0)" ::: "memory"); __builtin_amdgcn_s_barrier(); asm volatile("" ::: "memory");
;     FN_FINISH(r0, 0); FN_FINISH(r1, 1); FN_FINISH(r2, 2); FN_FINISH(r3, 3); FN_FINISH(r4, 4); FN_FINISH(r5, 5); FN_FINISH(r6, 6); FN_FINISH(r7, 7);
	v_add_f32_dpp v32, v32, v32 row_half_mirror row_mask:0xf bank_mask:0xf bound_ctrl:1
	v_mul_f32_e32 v58, v26, v58
	v_mul_f32_e32 v59, v27, v59
	v_mul_f32_e32 v56, v24, v56
	v_mul_f32_e32 v57, v25, v57
	v_add_f32_dpp v32, v32, v32 row_mirror row_mask:0xf bank_mask:0xf bound_ctrl:1
	global_store_dwordx4 v[64:65], v[56:59], off offset:2048
	v_readlane_b32 s4, v32, 16
	v_readlane_b32 s5, v32, 48
	v_readlane_b32 s0, v32, 0
	v_readlane_b32 s1, v32, 32
	v_mov_b32_e32 v32, s4
	v_mov_b32_e32 v33, s5
	v_add_f32_e32 v32, s0, v32
	v_add_f32_e32 v33, s1, v33
	s_nop 0
	v_add_f32_e32 v32, v32, v33
	v_fmac_f32_e32 v151, 0x3a000000, v32
	v_mul_f32_e32 v32, 0x4f800000, v151
	v_cmp_gt_f32_e32 vcc, s18, v151
	s_nop 1
	v_cndmask_b32_e32 v36, v151, v32, vcc
	v_sqrt_f32_e32 v37, v36
	v_mul_f32_e32 v32, v52, v50
	v_mul_f32_e32 v33, v53, v50
	v_add_u32_e32 v38, -1, v37
	v_fma_f32 v39, -v38, v37, v36
	v_cmp_ge_f32_e64 s[0:1], 0, v39
	v_add_u32_e32 v39, 1, v37
	v_mul_f32_e32 v32, v28, v32
	v_mul_f32_e32 v33, v29, v33
	v_cndmask_b32_e64 v38, v37, v38, s[0:1]
	v_fma_f32 v37, -v39, v37, v36
	v_cmp_lt_f32_e64 s[0:1], 0, v37
	global_store_dwordx4 v[64:65], v[32:35], off offset:3072
	s_nop 0
	v_cndmask_b32_e64 v37, v38, v39, s[0:1]
	v_mul_f32_e32 v38, 0x37800000, v37
	v_cndmask_b32_e32 v37, v37, v38, vcc
	v_cmp_class_f32_e32 vcc, v36, v152
	s_nop 1
	v_cndmask_b32_e32 v36, v37, v36, vcc
	v_div_scale_f32 v37, s[0:1], v36, v36, 1.0
	v_rcp_f32_e32 v38, v37
	s_lshl_b64 s[0:1], s[2:3], 2
	s_add_u32 s0, s24, s0
	s_addc_u32 s1, s25, s1
	v_fma_f32 v32, -v37, v38, 1.0
	v_fmac_f32_e32 v38, v32, v38
	v_div_scale_f32 v32, vcc, 1.0, v36, 1.0
	v_mul_f32_e32 v33, v32, v38
	v_fma_f32 v34, -v37, v33, v32
	v_fmac_f32_e32 v33, v34, v38
	v_fma_f32 v32, -v37, v33, v32
	v_div_fmas_f32 v32, v32, v38, v33
	v_div_fixup_f32 v32, v32, v36, 1.0
	v_mul_f32_e32 v36, v60, v32
	v_mul_f32_e32 v37, v61, v32
	v_mul_f32_e32 v38, v62, v32
	v_mul_f32_e32 v39, v63, v32
	v_mul_f32_e32 v0, v0, v36
	v_mul_f32_e32 v1, v1, v37
	v_mul_f32_e32 v2, v2, v38
	v_mul_f32_e32 v3, v3, v39
	global_store_dwordx4 v48, v[0:3], s[0:1]
	v_lshl_add_u64 v[34:35], s[0:1], 0, v[48:49]
	s_nop 0
	v_mul_f32_e32 v0, v46, v32
	v_mul_f32_e32 v1, v47, v32
	v_mul_f32_e32 v2, v66, v32
	v_mul_f32_e32 v3, v67, v32
	v_mul_f32_e32 v0, v4, v0
	v_mul_f32_e32 v1, v5, v1
	v_mul_f32_e32 v2, v6, v2
	v_mul_f32_e32 v3, v7, v3
	global_store_dwordx4 v48, v[0:3], s[0:1] offset:1024
	v_add_co_u32_e32 v4, vcc, s16, v34
	s_nop 0
	v_mul_f32_e32 v0, v68, v32
	v_mul_f32_e32 v1, v69, v32
	v_mul_f32_e32 v2, v70, v32
	v_mul_f32_e32 v3, v71, v32
	v_mul_f32_e32 v0, v8, v0
	v_mul_f32_e32 v1, v9, v1
	v_mul_f32_e32 v2, v10, v2
	v_mul_f32_e32 v3, v11, v3
	global_store_dwordx4 v48, v[0:3], s[0:1] offset:2048
	v_addc_co_u32_e32 v5, vcc, 0, v35, vcc
	s_nop 0
	v_mul_f32_e32 v0, v72, v32
	v_mul_f32_e32 v1, v73, v32
	v_mul_f32_e32 v2, v74, v32
	v_mul_f32_e32 v3, v75, v32
	v_mul_f32_e32 v0, v12, v0
	v_mul_f32_e32 v1, v13, v1
	v_mul_f32_e32 v2, v14, v2
	v_mul_f32_e32 v3, v15, v3
	global_store_dwordx4 v48, v[0:3], s[0:1] offset:3072
	s_nop 1
	v_mul_f32_e32 v0, v76, v32
	v_mul_f32_e32 v1, v77, v32
	v_mul_f32_e32 v2, v78, v32
	v_mul_f32_e32 v3, v79, v32
	v_mul_f32_e32 v0, v16, v0
	v_mul_f32_e32 v1, v17, v1
	v_mul_f32_e32 v2, v18, v2
	v_mul_f32_e32 v3, v19, v3
	global_store_dwordx4 v[4:5], v[0:3], off
	s_nop 1
	v_mul_f32_e32 v0, v40, v32
	v_mul_f32_e32 v1, v41, v32
	v_mul_f32_e32 v2, v42, v32
	v_mul_f32_e32 v3, v43, v32
	v_mul_f32_e32 v0, v20, v0
	v_mul_f32_e32 v1, v21, v1
	v_mul_f32_e32 v2, v22, v2
	v_mul_f32_e32 v3, v23, v3
	global_store_dwordx4 v[4:5], v[0:3], off offset:1024
	s_nop 1
	v_mul_f32_e32 v0, v44, v32
	v_mul_f32_e32 v1, v45, v32
	v_mul_f32_e32 v2, v80, v32
	v_mul_f32_e32 v3, v81, v32
	v_mul_f32_e32 v0, v24, v0
	v_mul_f32_e32 v1, v25, v1
	v_mul_f32_e32 v2, v26, v2
	v_mul_f32_e32 v3, v27, v3
	global_store_dwordx4 v[4:5], v[0:3], off offset:2048
	s_nop 1
	v_mul_f32_e32 v0, v82, v32
	v_mul_f32_e32 v1, v83, v32
	v_mul_f32_e32 v2, v84, v32
	v_mul_f32_e32 v3, v85, v32
	v_mul_f32_e32 v0, v28, v0
	v_mul_f32_e32 v1, v29, v1
	v_mul_f32_e32 v2, v30, v2
	v_mul_f32_e32 v3, v31, v3
	global_store_dwordx4 v[4:5], v[0:3], off offset:3072
